# v7: QK ds_read batching + nt on cmp-gather and sample-unit K/V once-read streams + EpiResid load batching + flat->global
# speedup vs baseline: 1.0054x; 1.0054x over previous
.LBB0_11:
	s_or_b64 exec, exec, s[6:7]
	s_memrealtime s[4:5]
	s_cmp_lt_i32 s90, 1
	s_waitcnt lgkmcnt(0)
	s_cselect_b64 s[4:5], -1, 0
	s_cmp_gt_i32 s91, 0
	s_cselect_b64 s[6:7], -1, 0
	s_and_b64 s[16:17], s[4:5], s[6:7]
	s_andn2_b64 vcc, exec, s[16:17]
	s_cbranch_vccnz .LBB0_673
	s_lshr_b32 s3, s2, 6
	s_lshl_b32 s2, s60, 3
	s_add_i32 s2, s3, s2
	s_min_i32 s13, s2, 0x53ff
	s_cmpk_lt_i32 s2, 0x5200
	s_cbranch_scc0 .LBB0_19
	s_mul_hi_i32 s4, s13, 0x63e7063f
	s_lshr_b32 s5, s4, 31
	s_ashr_i32 s4, s4, 12
	s_add_i32 s18, s4, s5
	s_mul_i32 s4, s18, 0x2900
	s_sub_i32 s22, s13, s4
	s_ashr_i32 s19, s18, 31
	s_mul_i32 s5, s18, 0x2a00000
	s_mul_hi_i32 s4, s18, 0x2a00000
	s_add_u32 s5, s94, s5
	s_addc_u32 s4, s95, s4
	s_add_u32 s6, s5, 0x200000
	s_addc_u32 s7, s4, 0
	s_cmpk_gt_i32 s22, 0xaff
	s_cbranch_scc0 .LBB0_20
	s_cmpk_gt_u32 s22, 0x107f
	s_cbranch_scc0 .LBB0_21
	s_cmpk_gt_u32 s22, 0x167f
	s_cbranch_scc0 .LBB0_22
	s_cmpk_gt_u32 s22, 0x187f
	s_cbranch_scc0 .LBB0_23
	s_cmpk_gt_u32 s22, 0x237f
	s_cbranch_scc0 .LBB0_24
	v_mov_b64_e32 v[2:3], s[0:1]
	global_load_dwordx2 v[2:3], v[2:3], off offset:192 sc0 sc1
	s_waitcnt vmcnt(0)
	s_add_u32 s8, s6, 0x2380000
	s_addc_u32 s9, s7, 0
	s_lshl_b32 s4, s22, 5
	s_lshl_b32 s5, s22, 1
	v_mov_b32_e32 v1, 0xb00000
	s_and_b32 s23, s4, 0x3e0
	s_and_b32 s4, s5, 0x7fffffc0
	s_add_i32 s12, s4, 0xffffb900
	s_mov_b64 s[10:11], 0
	s_waitcnt lgkmcnt(0)
	v_mad_i64_i32 v[2:3], s[4:5], s18, v1, v[2:3]
	s_branch .LBB0_25

.LBB0_25:
	s_andn2_b64 vcc, exec, s[10:11]
	s_cbranch_vccnz .LBB0_28
	v_mov_b64_e32 v[2:3], s[0:1]
	global_load_dwordx2 v[2:3], v[2:3], off offset:184 sc0 sc1
	s_waitcnt vmcnt(0)
	s_add_i32 s4, s22, 0xe780
	s_and_b32 s5, s4, 0xffff
	s_mul_i32 s5, s5, 0xba2f
	s_lshr_b32 s5, s5, 23
	s_mul_i32 s8, s5, 0xb0
	s_sub_i32 s4, s4, s8
	s_lshl_b32 s8, s4, 5
	s_and_b32 s23, s8, 0xffe0
	s_and_b32 s4, s4, 0xffff
	s_cmpk_gt_u32 s4, 0x57
	s_cbranch_scc0 .LBB0_29
	s_lshl_b32 s4, s23, 1
	s_add_i32 s4, s4, 0x7fffea00
	s_and_b32 s4, s4, 0x7fffff00
	s_and_b32 s8, s23, 0x60
	s_or_b32 s4, s8, s4
	s_bitset1_b32 s4, 7
	s_mov_b64 s[8:9], 0
	s_branch .LBB0_30

.LBB0_34:
	s_andn2_b64 vcc, exec, s[20:21]
	s_cbranch_vccnz .LBB0_36
	v_mov_b64_e32 v[2:3], s[0:1]
	global_load_dwordx2 v[2:3], v[2:3], off offset:176 sc0 sc1
	s_waitcnt vmcnt(0)
	s_lshl_b64 s[20:21], s[18:19], 22
	s_add_u32 s8, s6, 0x1680000
	s_addc_u32 s9, s7, 0
	s_lshl_b32 s4, s22, 5
	s_lshl_b32 s12, s22, 1
	s_and_b32 s23, s4, 0x3e0
	s_and_b32 s4, s12, 0x3fc0
	s_mov_b64 s[10:11], 0x400
	s_movk_i32 s5, 0x400
	s_add_i32 s12, s4, 0xffffd300
	s_mov_b32 s4, s23
	s_waitcnt lgkmcnt(0)
	v_lshl_add_u64 v[2:3], v[2:3], 0, s[20:21]

.LBB0_37:
	s_andn2_b64 vcc, exec, s[20:21]
	s_cbranch_vccnz .LBB0_39
	v_mov_b64_e32 v[2:3], s[0:1]
	global_load_dwordx2 v[2:3], v[2:3], off offset:112 sc0 sc1
	s_waitcnt vmcnt(0)
	s_add_i32 s4, s22, 0xef80
	s_and_b32 s8, s4, 0xffff
	s_mul_i32 s8, s8, 0xaaab
	s_lshr_b32 s12, s8, 16
	s_lshr_b32 s8, s8, 22
	s_mulk_i32 s8, 0x60
	s_sub_i32 s4, s4, s8
	s_add_u32 s8, s6, 0x1080000
	s_addc_u32 s9, s7, 0
	s_lshl_b32 s4, s4, 5
	v_mov_b32_e32 v1, 0xb28000
	s_and_b32 s23, s4, 0xffe0
	s_mov_b64 s[10:11], 0x400
	s_movk_i32 s5, 0xb28
	s_and_b32 s12, s12, 0xffc0
	s_mov_b32 s4, s23
	s_waitcnt lgkmcnt(0)
	v_mad_i64_i32 v[2:3], s[20:21], s18, v1, v[2:3]

.LBB0_40:
	v_mov_b64_e32 v[2:3], s[0:1]
	global_load_dwordx2 v[2:3], v[2:3], off offset:104 sc0 sc1
	s_waitcnt vmcnt(0)
	s_add_u32 s8, s6, 0xb00000
	s_addc_u32 s9, s7, 0
	s_lshl_b32 s4, s22, 5
	s_lshl_b32 s12, s22, 1
	v_mov_b32_e32 v1, 0xb00000
	s_and_b32 s23, s4, 0x3e0
	s_and_b32 s4, s12, 0x3fc0
	s_mov_b64 s[10:11], 0xb00
	s_movk_i32 s5, 0x400
	s_add_i32 s12, s4, 0xffffea00
	s_mov_b32 s4, s23
	s_waitcnt lgkmcnt(0)
	v_mad_i64_i32 v[2:3], s[20:21], s18, v1, v[2:3]

.LBB0_42:
	v_mov_b64_e32 v[2:3], s[0:1]
	global_load_dwordx2 v[2:3], v[2:3], off offset:96 sc0 sc1
	s_waitcnt vmcnt(0)
	s_mul_i32 s4, s22, 0xba3
	s_lshr_b32 s5, s4, 31
	s_ashr_i32 s4, s4, 19
	s_add_i32 s5, s4, s5
	s_mul_i32 s4, s5, 0xb0
	s_sub_i32 s4, s22, s4
	s_sext_i32_i16 s4, s4
	s_lshl_b32 s23, s4, 5
	s_cmpk_gt_i32 s4, 0x57
	s_cbranch_scc0 .LBB0_44
	s_lshl_b32 s4, s4, 6
	s_add_i32 s4, s4, 0x7fffea00
	s_and_b32 s4, s4, 0x7fffff00
	s_and_b32 s8, s23, 0x60
	s_or_b32 s4, s8, s4
	s_bitset1_b32 s4, 7
	s_cbranch_execz .LBB0_45
	s_branch .LBB0_46

.LBB0_48:
	v_mov_b64_e32 v[2:3], s[0:1]
	global_load_dwordx2 v[2:3], v[2:3], off offset:128 sc0 sc1
	s_waitcnt vmcnt(0)
	s_add_i32 s4, s13, 0xffffae00
	s_bfe_u32 s12, s13, 0x10006
	s_mov_b32 s7, 0
	s_lshr_b32 s6, s4, 7
	s_lshl_b32 s10, s12, 19
	s_mov_b32 s11, s7
	s_lshl_b64 s[18:19], s[6:7], 20
	s_lshl_b64 s[6:7], s[6:7], 19
	s_add_u32 s4, s94, s6
	s_addc_u32 s6, s95, s7
	s_add_u32 s8, s4, 0x28a00000
	s_addc_u32 s9, s6, 0
	s_lshl_b32 s6, s13, 5
	s_lshl_b32 s4, s12, 7
	s_lshl_b32 s7, s13, 4
	s_and_b32 s23, s6, 0x60
	s_movk_i32 s5, 0x80
	s_and_b32 s12, s7, 0x3c0
	s_or_b32 s4, s4, s23
	s_waitcnt lgkmcnt(0)
	v_lshl_add_u64 v[2:3], v[2:3], 0, s[18:19]
	v_lshl_add_u64 v[2:3], v[2:3], 0, s[10:11]
	s_mov_b64 s[10:11], 0x400

.LBB0_114:
	s_add_i32 s34, s13, s6
	s_cmpk_lt_i32 s34, 0x5400
	s_cselect_b64 s[20:21], -1, 0
	s_and_b64 s[22:23], s[20:21], exec
	s_cselect_b32 s36, s34, 0x53ff
	s_cmpk_lt_i32 s36, 0x5200
	s_mov_b64 s[38:39], -1
	s_cbranch_scc0 .LBB0_143
	s_mul_hi_i32 s18, s36, 0x63e7063f
	s_lshr_b32 s22, s18, 31
	s_ashr_i32 s18, s18, 12
	s_add_i32 s40, s18, s22
	s_mul_i32 s18, s40, 0x2900
	s_sub_i32 s18, s36, s18
	s_ashr_i32 s41, s40, 31
	s_mul_i32 s23, s40, 0x2a00000
	s_mul_hi_i32 s22, s40, 0x2a00000
	s_add_u32 s38, s5, s23
	s_addc_u32 s39, s7, s22
	s_cmpk_gt_i32 s18, 0xaff
	s_mov_b64 s[42:43], -1
	s_cbranch_scc0 .LBB0_136
	s_cmpk_gt_u32 s18, 0x107f
	s_cbranch_scc0 .LBB0_133
	s_cmpk_gt_u32 s18, 0x167f
	s_cbranch_scc0 .LBB0_130
	s_cmpk_gt_u32 s18, 0x187f
	s_cbranch_scc0 .LBB0_127
	s_cmpk_gt_u32 s18, 0x237f
	s_mov_b64 s[24:25], -1
	s_cbranch_scc0 .LBB0_121
	v_mov_b64_e32 v[34:35], s[0:1]
	global_load_dwordx2 v[34:35], v[34:35], off offset:192 sc0 sc1
	s_waitcnt vmcnt(0)
	s_add_u32 s22, s38, 0x2380000
	s_addc_u32 s23, s39, 0
	s_lshl_b32 s24, s18, 5
	s_lshl_b32 s25, s18, 1
	s_and_b32 s37, s24, 0x3e0
	s_and_b32 s24, s25, 0x7fffffc0
	s_add_i32 s26, s24, 0xffffb900
	s_waitcnt lgkmcnt(0)
	v_mad_i64_i32 v[34:35], s[24:25], s40, v110, v[34:35]
	s_mov_b64 s[24:25], 0
.LBB0_121:
	s_andn2_b64 vcc, exec, s[24:25]
	s_cbranch_vccnz .LBB0_274
	v_mov_b64_e32 v[34:35], s[0:1]
	global_load_dwordx2 v[34:35], v[34:35], off offset:184 sc0 sc1
	s_waitcnt vmcnt(0)
	s_add_i32 s22, s18, 0xe780
	s_and_b32 s23, s22, 0xffff
	s_mul_i32 s23, s23, 0xba2f
	s_lshr_b32 s24, s23, 23
	s_mul_i32 s23, s24, 0xb0
	s_sub_i32 s22, s22, s23
	s_lshl_b32 s23, s22, 5
	s_and_b32 s37, s23, 0xffe0
	s_and_b32 s22, s22, 0xffff
	s_cmpk_gt_u32 s22, 0x57
	s_mov_b64 s[22:23], -1
	s_cbranch_scc0 .LBB0_124
	s_lshl_b32 s22, s37, 1
	s_add_i32 s22, s22, 0x7fffea00
	s_and_b32 s22, s22, 0x7fffff00
	s_and_b32 s23, s37, 0x60
	s_or_b32 s22, s23, s22
	s_or_b32 s35, s22, 0x80
	s_mov_b64 s[22:23], 0

.LBB0_128:
	v_mov_b64_e32 v[34:35], s[0:1]
	global_load_dwordx2 v[34:35], v[34:35], off offset:176 sc0 sc1
	s_waitcnt vmcnt(0)
	s_lshl_b64 s[42:43], s[40:41], 22
	s_add_u32 s22, s38, 0x1680000
	s_addc_u32 s23, s39, 0
	s_lshl_b32 s26, s18, 5
	s_lshl_b32 s35, s18, 1
	s_and_b32 s37, s26, 0x3e0
	s_and_b32 s26, s35, 0x3fc0
	s_mov_b64 s[24:25], 0x400
	s_movk_i32 s27, 0x400
	s_addk_i32 s26, 0xd300
	s_mov_b32 s35, s37
	s_waitcnt lgkmcnt(0)
	v_lshl_add_u64 v[34:35], v[34:35], 0, s[42:43]

.LBB0_130:
	s_andn2_b64 vcc, exec, s[42:43]
	s_cbranch_vccnz .LBB0_132
	v_mov_b64_e32 v[34:35], s[0:1]
	global_load_dwordx2 v[34:35], v[34:35], off offset:112 sc0 sc1
	s_waitcnt vmcnt(0)
	s_add_i32 s22, s18, 0xef80
	s_and_b32 s23, s22, 0xffff
	s_mul_i32 s23, s23, 0xaaab
	s_lshr_b32 s26, s23, 16
	s_lshr_b32 s23, s23, 22
	s_mulk_i32 s23, 0x60
	s_sub_i32 s35, s22, s23
	s_add_u32 s22, s38, 0x1080000
	s_addc_u32 s23, s39, 0
	s_lshl_b32 s35, s35, 5
	s_and_b32 s37, s35, 0xffe0
	s_mov_b64 s[24:25], 0x400
	s_movk_i32 s27, 0xb28
	s_and_b32 s26, s26, 0xffc0
	s_mov_b32 s35, s37
	s_waitcnt lgkmcnt(0)
	v_mad_i64_i32 v[34:35], s[42:43], s40, v112, v[34:35]

.LBB0_133:
	s_andn2_b64 vcc, exec, s[42:43]
	s_cbranch_vccnz .LBB0_135
	v_mov_b64_e32 v[34:35], s[0:1]
	global_load_dwordx2 v[34:35], v[34:35], off offset:104 sc0 sc1
	s_waitcnt vmcnt(0)
	s_add_u32 s22, s38, 0xb00000
	s_addc_u32 s23, s39, 0
	s_lshl_b32 s26, s18, 5
	s_lshl_b32 s35, s18, 1
	s_and_b32 s37, s26, 0x3e0
	s_and_b32 s26, s35, 0x3fc0
	s_mov_b64 s[24:25], 0xb00
	s_movk_i32 s27, 0x400
	s_addk_i32 s26, 0xea00
	s_mov_b32 s35, s37
	s_waitcnt lgkmcnt(0)
	v_mad_i64_i32 v[34:35], s[42:43], s40, v110, v[34:35]

.LBB0_136:
	s_andn2_b64 vcc, exec, s[42:43]
	s_cbranch_vccnz .LBB0_142
	v_mov_b64_e32 v[34:35], s[0:1]
	global_load_dwordx2 v[34:35], v[34:35], off offset:96 sc0 sc1
	s_waitcnt vmcnt(0)
	s_mul_i32 s22, s18, 0xba3
	s_lshr_b32 s23, s22, 31
	s_ashr_i32 s24, s22, 19
	s_add_i32 s24, s24, s23
	s_mul_i32 s22, s24, 0xb0
	s_sub_i32 s18, s18, s22
	s_sext_i32_i16 s18, s18
	s_lshl_b32 s37, s18, 5
	s_cmpk_gt_i32 s18, 0x57
	s_mov_b64 s[22:23], -1
	s_cbranch_scc0 .LBB0_139
	s_lshl_b32 s18, s18, 6
	s_add_i32 s18, s18, 0x7fffea00
	s_and_b32 s18, s18, 0x7fffff00
	s_and_b32 s22, s37, 0x60
	s_or_b32 s18, s22, s18
	s_or_b32 s35, s18, 0x80
	s_mov_b64 s[22:23], 0

.LBB0_143:
	s_andn2_b64 vcc, exec, s[38:39]
	s_cbranch_vccnz .LBB0_145
	v_mov_b64_e32 v[34:35], s[0:1]
	global_load_dwordx2 v[34:35], v[34:35], off offset:128 sc0 sc1
	s_waitcnt vmcnt(0)
	s_add_i32 s18, s36, 0xffffae00
	s_bfe_u32 s26, s36, 0x10006
	s_lshr_b32 s18, s18, 7
	s_lshl_b32 s24, s26, 19
	s_lshl_b64 s[38:39], s[18:19], 20
	s_lshl_b64 s[22:23], s[18:19], 19
	s_add_u32 s22, s28, s22
	s_addc_u32 s23, s29, s23
	s_lshl_b32 s18, s26, 7
	s_lshl_b32 s26, s36, 5
	s_mov_b32 s25, s19
	s_lshl_b32 s35, s36, 4
	s_and_b32 s37, s26, 0x60
	s_movk_i32 s27, 0x80
	s_and_b32 s26, s35, 0x3c0
	s_or_b32 s35, s18, s37
	s_waitcnt lgkmcnt(0)
	v_lshl_add_u64 v[34:35], v[34:35], 0, s[38:39]
	v_lshl_add_u64 v[34:35], v[34:35], 0, s[24:25]
	s_mov_b64 s[24:25], 0x400

.LBB0_177:
	s_or_b64 exec, exec, s[38:39]
	v_add_u32_e32 v146, 0x400, v113
	v_add_u32_e32 v147, 0x800, v113
	v_add_u32_e32 v148, 0xc00, v113
	v_add_u32_e32 v149, 0x1000, v113
	v_add_u32_e32 v150, 0x1400, v113
	v_add_u32_e32 v151, 0x1800, v113
	v_add_u32_e32 v152, 0x1c00, v113
	s_waitcnt vmcnt(0)
	ds_write2_b32 v113, v2, v3 offset1:66
	ds_write2_b32 v113, v4, v5 offset0:132 offset1:198
	ds_write2_b32 v146, v6, v7 offset0:8 offset1:74
	ds_write2_b32 v146, v8, v9 offset0:140 offset1:206
	ds_write2_b32 v147, v10, v11 offset0:16 offset1:82
	ds_write2_b32 v147, v12, v13 offset0:148 offset1:214
	ds_write2_b32 v148, v14, v15 offset0:24 offset1:90
	ds_write2_b32 v148, v16, v17 offset0:156 offset1:222
	ds_write2_b32 v149, v18, v19 offset0:32 offset1:98
	ds_write2_b32 v149, v20, v21 offset0:164 offset1:230
	ds_write2_b32 v150, v22, v23 offset0:40 offset1:106
	ds_write2_b32 v150, v24, v25 offset0:172 offset1:238
	ds_write2_b32 v151, v26, v27 offset0:48 offset1:114
	ds_write2_b32 v151, v28, v29 offset0:180 offset1:246
	ds_write2_b32 v152, v30, v31 offset0:56 offset1:122
	ds_write2_b32 v152, v32, v33 offset0:188 offset1:254
	s_waitcnt lgkmcnt(0)
	ds_read2_b32 v[6:7], v106 offset1:8
	ds_read2_b32 v[8:9], v106 offset0:33 offset1:41
	ds_read2_b32 v[10:11], v106 offset0:66 offset1:74
	ds_read2_b32 v[12:13], v106 offset0:99 offset1:107
	ds_read2_b32 v[14:15], v106 offset0:132 offset1:140
	s_waitcnt lgkmcnt(4)
	v_bfe_u32 v2, v6, 16, 1
	v_add3_u32 v2, v6, v2, s31
	s_waitcnt lgkmcnt(3)
	v_bfe_u32 v3, v8, 16, 1
	v_lshrrev_b32_e32 v2, 16, v2
	v_add3_u32 v3, v8, v3, s31
	ds_read2_b32 v[16:17], v106 offset0:165 offset1:173
	v_and_or_b32 v2, v3, s33, v2
	s_waitcnt lgkmcnt(3)
	v_bfe_u32 v3, v10, 16, 1
	v_add3_u32 v3, v10, v3, s31
	s_waitcnt lgkmcnt(2)
	v_bfe_u32 v4, v12, 16, 1
	ds_read2_b32 v[18:19], v106 offset0:198 offset1:206
	v_lshrrev_b32_e32 v3, 16, v3
	v_add3_u32 v4, v12, v4, s31
	ds_read2_b32 v[20:21], v106 offset0:231 offset1:239
	v_and_or_b32 v3, v4, s33, v3
	s_waitcnt lgkmcnt(3)
	v_bfe_u32 v4, v14, 16, 1
	v_add3_u32 v4, v14, v4, s31
	s_waitcnt lgkmcnt(2)
	v_bfe_u32 v5, v16, 16, 1
	v_lshrrev_b32_e32 v4, 16, v4
	v_add3_u32 v5, v16, v5, s31
	v_and_or_b32 v4, v5, s33, v4
	s_waitcnt lgkmcnt(1)
	v_bfe_u32 v5, v18, 16, 1
	v_add3_u32 v5, v18, v5, s31
	s_waitcnt lgkmcnt(0)
	v_bfe_u32 v6, v20, 16, 1
	v_lshrrev_b32_e32 v5, 16, v5
	v_add3_u32 v6, v20, v6, s31
	v_and_or_b32 v5, v6, s33, v5
	v_add_u32_e32 v6, s4, v105
	v_ashrrev_i32_e32 v8, 31, v6
	v_mul_lo_u32 v8, s10, v8
	v_mul_lo_u32 v10, s11, v6
	v_mad_u64_u32 v[22:23], s[36:37], s10, v6, 0
	s_add_i32 s18, s30, s13
	v_add3_u32 v23, v23, v8, v10
	s_ashr_i32 s13, s12, 31
	v_lshl_add_u64 v[22:23], v[22:23], 1, s[8:9]
	s_lshl_b64 s[12:13], s[12:13], 1
	v_lshl_add_u64 v[22:23], v[22:23], 0, s[12:13]
	v_lshl_add_u64 v[22:23], v[22:23], 0, v[100:101]
	global_store_dwordx4 v[22:23], v[2:5], off
	v_bfe_u32 v6, v21, 16, 1
	v_add3_u32 v6, v21, v6, s31
	v_bfe_u32 v2, v7, 16, 1
	v_add3_u32 v2, v7, v2, s31
	v_bfe_u32 v3, v9, 16, 1
	v_lshrrev_b32_e32 v2, 16, v2
	v_add3_u32 v3, v9, v3, s31
	v_and_or_b32 v2, v3, s33, v2
	v_bfe_u32 v3, v11, 16, 1
	v_add3_u32 v3, v11, v3, s31
	v_bfe_u32 v4, v13, 16, 1
	v_lshrrev_b32_e32 v3, 16, v3
	v_add3_u32 v4, v13, v4, s31
	v_and_or_b32 v3, v4, s33, v3
	v_bfe_u32 v4, v15, 16, 1
	v_add3_u32 v4, v15, v4, s31
	v_bfe_u32 v5, v17, 16, 1
	v_lshrrev_b32_e32 v4, 16, v4
	v_add3_u32 v5, v17, v5, s31
	v_and_or_b32 v4, v5, s33, v4
	v_bfe_u32 v5, v19, 16, 1
	v_add3_u32 v5, v19, v5, s31
	v_lshrrev_b32_e32 v5, 16, v5
	v_and_or_b32 v5, v6, s33, v5
	v_add_u32_e32 v6, s4, v107
	v_ashrrev_i32_e32 v7, 31, v6
	v_mul_lo_u32 v8, s10, v7
	v_mul_lo_u32 v9, s11, v6
	v_mad_u64_u32 v[6:7], s[36:37], s10, v6, 0
	v_add3_u32 v7, v7, v8, v9
	v_lshl_add_u64 v[6:7], v[6:7], 1, s[8:9]
	v_lshl_add_u64 v[6:7], v[6:7], 0, s[12:13]
	ds_read2_b32 v[8:9], v106 offset0:16 offset1:24
	v_lshl_add_u64 v[6:7], v[6:7], 0, v[100:101]
	global_store_dwordx4 v[6:7], v[2:5], off
	ds_read2_b32 v[6:7], v106 offset0:49 offset1:57
	ds_read2_b32 v[10:11], v106 offset0:82 offset1:90
	ds_read2_b32 v[12:13], v106 offset0:115 offset1:123
	s_waitcnt lgkmcnt(3)
	v_bfe_u32 v2, v8, 16, 1
	v_add3_u32 v2, v8, v2, s31
	s_waitcnt lgkmcnt(2)
	v_bfe_u32 v3, v6, 16, 1
	ds_read2_b32 v[14:15], v106 offset0:148 offset1:156
	v_lshrrev_b32_e32 v2, 16, v2
	v_add3_u32 v3, v6, v3, s31
	ds_read2_b32 v[16:17], v106 offset0:181 offset1:189
	v_and_or_b32 v2, v3, s33, v2
	s_waitcnt lgkmcnt(3)
	v_bfe_u32 v3, v10, 16, 1
	v_add3_u32 v3, v10, v3, s31
	s_waitcnt lgkmcnt(2)
	v_bfe_u32 v4, v12, 16, 1
	ds_read2_b32 v[18:19], v106 offset0:214 offset1:222
	v_lshrrev_b32_e32 v3, 16, v3
	v_add3_u32 v4, v12, v4, s31
	ds_read2_b32 v[20:21], v106 offset0:247 offset1:255
	v_and_or_b32 v3, v4, s33, v3
	s_waitcnt lgkmcnt(3)
	v_bfe_u32 v4, v14, 16, 1
	v_add3_u32 v4, v14, v4, s31
	s_waitcnt lgkmcnt(2)
	v_bfe_u32 v5, v16, 16, 1
	v_lshrrev_b32_e32 v4, 16, v4
	v_add3_u32 v5, v16, v5, s31
	v_and_or_b32 v4, v5, s33, v4
	s_waitcnt lgkmcnt(1)
	v_bfe_u32 v5, v18, 16, 1
	v_add3_u32 v5, v18, v5, s31
	s_waitcnt lgkmcnt(0)
	v_bfe_u32 v6, v20, 16, 1
	v_lshrrev_b32_e32 v5, 16, v5
	v_add3_u32 v6, v20, v6, s31
	v_and_or_b32 v5, v6, s33, v5
	v_add_u32_e32 v6, s4, v108
	v_ashrrev_i32_e32 v8, 31, v6
	v_mul_lo_u32 v8, s10, v8
	v_mul_lo_u32 v10, s11, v6
	v_mad_u64_u32 v[22:23], s[36:37], s10, v6, 0
	v_add3_u32 v23, v23, v8, v10
	v_lshl_add_u64 v[22:23], v[22:23], 1, s[8:9]
	v_lshl_add_u64 v[22:23], v[22:23], 0, s[12:13]
	v_lshl_add_u64 v[22:23], v[22:23], 0, v[100:101]
	global_store_dwordx4 v[22:23], v[2:5], off
	v_bfe_u32 v6, v21, 16, 1
	v_add3_u32 v6, v21, v6, s31
	v_bfe_u32 v2, v9, 16, 1
	v_add3_u32 v2, v9, v2, s31
	v_bfe_u32 v3, v7, 16, 1
	v_lshrrev_b32_e32 v2, 16, v2
	v_add3_u32 v3, v7, v3, s31
	v_and_or_b32 v2, v3, s33, v2
	v_bfe_u32 v3, v11, 16, 1
	v_add3_u32 v3, v11, v3, s31
	v_bfe_u32 v4, v13, 16, 1
	v_lshrrev_b32_e32 v3, 16, v3
	v_add3_u32 v4, v13, v4, s31
	v_and_or_b32 v3, v4, s33, v3
	v_bfe_u32 v4, v15, 16, 1
	v_add3_u32 v4, v15, v4, s31
	v_bfe_u32 v5, v17, 16, 1
	v_lshrrev_b32_e32 v4, 16, v4
	v_add3_u32 v5, v17, v5, s31
	v_and_or_b32 v4, v5, s33, v4
	v_bfe_u32 v5, v19, 16, 1
	v_add3_u32 v5, v19, v5, s31
	v_lshrrev_b32_e32 v5, 16, v5
	v_and_or_b32 v5, v6, s33, v5
	v_add_u32_e32 v6, s4, v109
	v_ashrrev_i32_e32 v7, 31, v6
	v_mul_lo_u32 v8, s10, v7
	v_mul_lo_u32 v9, s11, v6
	v_mad_u64_u32 v[6:7], s[10:11], s10, v6, 0
	v_add3_u32 v7, v7, v8, v9
	v_lshl_add_u64 v[6:7], v[6:7], 1, s[8:9]
	v_lshl_add_u64 v[6:7], v[6:7], 0, s[12:13]
	v_lshl_add_u64 v[6:7], v[6:7], 0, v[100:101]
	global_store_dwordx4 v[6:7], v[2:5], off
	s_waitcnt lgkmcnt(0)
	s_min_i32 s27, s18, 0x53ff
	s_cmpk_lt_i32 s18, 0x5200
	s_mov_b64 s[38:39], -1
	s_cbranch_scc0 .LBB0_206
	s_mul_hi_i32 s4, s27, 0x63e7063f
	s_lshr_b32 s8, s4, 31
	s_ashr_i32 s4, s4, 12
	s_add_i32 s40, s4, s8
	s_mul_i32 s4, s40, 0x2900
	s_sub_i32 s18, s27, s4
	s_ashr_i32 s41, s40, 31
	s_mul_i32 s8, s40, 0x2a00000
	s_mul_hi_i32 s4, s40, 0x2a00000
	s_add_u32 s38, s5, s8
	s_addc_u32 s39, s7, s4
	s_cmpk_gt_i32 s18, 0xaff
	s_mov_b64 s[42:43], -1
	s_cbranch_scc0 .LBB0_199
	s_cmpk_gt_u32 s18, 0x107f
	s_cbranch_scc0 .LBB0_196
	s_cmpk_gt_u32 s18, 0x167f
	s_cbranch_scc0 .LBB0_193
	s_cmpk_gt_u32 s18, 0x187f
	s_cbranch_scc0 .LBB0_190
	s_cmpk_gt_u32 s18, 0x237f
	s_mov_b64 s[10:11], -1
	s_cbranch_scc0 .LBB0_184
	v_mov_b64_e32 v[2:3], s[0:1]
	global_load_dwordx2 v[2:3], v[2:3], off offset:192 sc0 sc1
	s_waitcnt vmcnt(0)
	s_add_u32 s8, s38, 0x2380000
	s_addc_u32 s9, s39, 0
	s_lshl_b32 s4, s18, 5
	s_lshl_b32 s10, s18, 1
	s_and_b32 s36, s4, 0x3e0
	s_and_b32 s4, s10, 0x7fffffc0
	s_add_i32 s12, s4, 0xffffb900
	s_waitcnt lgkmcnt(0)
	v_mad_i64_i32 v[34:35], s[10:11], s40, v110, v[2:3]
	s_mov_b64 s[10:11], 0
.LBB0_184:
	s_andn2_b64 vcc, exec, s[10:11]
	s_cbranch_vccnz .LBB0_275
	v_mov_b64_e32 v[2:3], s[0:1]
	global_load_dwordx2 v[2:3], v[2:3], off offset:184 sc0 sc1
	s_waitcnt vmcnt(0)
	s_add_i32 s4, s18, 0xe780
	s_and_b32 s8, s4, 0xffff
	s_mul_i32 s8, s8, 0xba2f
	s_lshr_b32 s10, s8, 23
	s_mul_i32 s8, s10, 0xb0
	s_sub_i32 s4, s4, s8
	s_lshl_b32 s8, s4, 5
	s_and_b32 s36, s8, 0xffe0
	s_and_b32 s4, s4, 0xffff
	s_cmpk_gt_u32 s4, 0x57
	s_mov_b64 s[8:9], -1
	s_cbranch_scc0 .LBB0_187
	s_lshl_b32 s4, s36, 1
	s_add_i32 s4, s4, 0x7fffea00
	s_and_b32 s4, s4, 0x7fffff00
	s_and_b32 s8, s36, 0x60
	s_or_b32 s4, s8, s4
	s_bitset1_b32 s4, 7
	s_mov_b64 s[8:9], 0

.LBB0_191:
	v_mov_b64_e32 v[2:3], s[0:1]
	global_load_dwordx2 v[2:3], v[2:3], off offset:176 sc0 sc1
	s_waitcnt vmcnt(0)
	s_lshl_b64 s[42:43], s[40:41], 22
	s_add_u32 s8, s38, 0x1680000
	s_addc_u32 s9, s39, 0
	s_lshl_b32 s4, s18, 5
	s_lshl_b32 s12, s18, 1
	s_and_b32 s36, s4, 0x3e0
	s_and_b32 s4, s12, 0x3fc0
	s_mov_b64 s[10:11], 0x400
	s_movk_i32 s13, 0x400
	s_add_i32 s12, s4, 0xffffd300
	s_mov_b32 s4, s36
	s_waitcnt lgkmcnt(0)
	v_lshl_add_u64 v[34:35], v[2:3], 0, s[42:43]

.LBB0_193:
	s_andn2_b64 vcc, exec, s[42:43]
	s_cbranch_vccnz .LBB0_195
	v_mov_b64_e32 v[2:3], s[0:1]
	global_load_dwordx2 v[2:3], v[2:3], off offset:112 sc0 sc1
	s_waitcnt vmcnt(0)
	s_add_i32 s4, s18, 0xef80
	s_and_b32 s8, s4, 0xffff
	s_mul_i32 s8, s8, 0xaaab
	s_lshr_b32 s12, s8, 16
	s_lshr_b32 s8, s8, 22
	s_mulk_i32 s8, 0x60
	s_sub_i32 s4, s4, s8
	s_add_u32 s8, s38, 0x1080000
	s_addc_u32 s9, s39, 0
	s_lshl_b32 s4, s4, 5
	s_and_b32 s36, s4, 0xffe0
	s_mov_b64 s[10:11], 0x400
	s_movk_i32 s13, 0xb28
	s_and_b32 s12, s12, 0xffc0
	s_mov_b32 s4, s36
	s_waitcnt lgkmcnt(0)
	v_mad_i64_i32 v[34:35], s[42:43], s40, v112, v[2:3]

.LBB0_196:
	s_andn2_b64 vcc, exec, s[42:43]
	s_cbranch_vccnz .LBB0_198
	v_mov_b64_e32 v[2:3], s[0:1]
	global_load_dwordx2 v[2:3], v[2:3], off offset:104 sc0 sc1
	s_waitcnt vmcnt(0)
	s_add_u32 s8, s38, 0xb00000
	s_addc_u32 s9, s39, 0
	s_lshl_b32 s4, s18, 5
	s_lshl_b32 s12, s18, 1
	s_and_b32 s36, s4, 0x3e0
	s_and_b32 s4, s12, 0x3fc0
	s_mov_b64 s[10:11], 0xb00
	s_movk_i32 s13, 0x400
	s_add_i32 s12, s4, 0xffffea00
	s_mov_b32 s4, s36
	s_waitcnt lgkmcnt(0)
	v_mad_i64_i32 v[34:35], s[42:43], s40, v110, v[2:3]

.LBB0_199:
	s_andn2_b64 vcc, exec, s[42:43]
	s_cbranch_vccnz .LBB0_205
	v_mov_b64_e32 v[2:3], s[0:1]
	global_load_dwordx2 v[2:3], v[2:3], off offset:96 sc0 sc1
	s_waitcnt vmcnt(0)
	s_mul_i32 s4, s18, 0xba3
	s_lshr_b32 s8, s4, 31
	s_ashr_i32 s10, s4, 19
	s_add_i32 s10, s10, s8
	s_mul_i32 s4, s10, 0xb0
	s_sub_i32 s4, s18, s4
	s_sext_i32_i16 s11, s4
	s_lshl_b32 s36, s11, 5
	s_cmpk_gt_i32 s11, 0x57
	s_mov_b64 s[8:9], -1
	s_cbranch_scc0 .LBB0_202
	s_lshl_b32 s4, s11, 6
	s_add_i32 s4, s4, 0x7fffea00
	s_and_b32 s4, s4, 0x7fffff00
	s_and_b32 s8, s36, 0x60
	s_or_b32 s4, s8, s4
	s_bitset1_b32 s4, 7
	s_mov_b64 s[8:9], 0

.LBB0_206:
	s_andn2_b64 vcc, exec, s[38:39]
	s_cbranch_vccnz .LBB0_208
	v_mov_b64_e32 v[2:3], s[0:1]
	global_load_dwordx2 v[2:3], v[2:3], off offset:128 sc0 sc1
	s_waitcnt vmcnt(0)
	s_add_i32 s4, s27, 0xffffae00
	s_bfe_u32 s12, s27, 0x10006
	s_lshr_b32 s18, s4, 7
	s_lshl_b32 s10, s12, 19
	s_lshl_b64 s[38:39], s[18:19], 20
	s_lshl_b64 s[8:9], s[18:19], 19
	s_add_u32 s8, s28, s8
	s_addc_u32 s9, s29, s9
	s_lshl_b32 s4, s12, 7
	s_lshl_b32 s12, s27, 5
	s_mov_b32 s11, s19
	s_lshl_b32 s18, s27, 4
	s_and_b32 s36, s12, 0x60
	s_movk_i32 s13, 0x80
	s_and_b32 s12, s18, 0x3c0
	s_or_b32 s4, s4, s36
	s_waitcnt lgkmcnt(0)
	v_lshl_add_u64 v[2:3], v[2:3], 0, s[38:39]
	v_lshl_add_u64 v[34:35], v[2:3], 0, s[10:11]
	s_mov_b64 s[10:11], 0x400

.LBB0_279:
	s_add_i32 s4, s6, 0xffffff80
	s_cmp_ge_i32 s2, s4
	s_cbranch_scc0 .LBB0_283
	s_waitcnt vmcnt(0)
	v_mov_b64_e32 v[2:3], s[0:1]
	global_load_dwordx2 v[4:5], v[2:3], off offset:120 sc0 sc1
	s_waitcnt vmcnt(0)
	global_load_dwordx2 v[6:7], v[2:3], off offset:128 sc0 sc1
	s_waitcnt vmcnt(0)
	s_sub_i32 s4, s2, s4
	s_mov_b32 s7, 0
	s_lshr_b32 s6, s4, 5
	s_and_b32 s4, s4, 31
	s_lshl_b64 s[22:23], s[6:7], 20
	s_mov_b32 s19, s7
	s_lshl_b64 s[20:21], s[6:7], 13
	s_lshl_b32 s18, s4, 15
	v_mov_b32_e32 v3, 0
	v_lshlrev_b32_e32 v2, 2, v98
	s_mov_b32 s13, s7
	s_lshl_b32 s12, s4, 8
	s_mov_b64 s[8:9], 0
	s_movk_i32 s2, 0x1000
	s_mov_b64 s[10:11], 0x2000
	s_waitcnt lgkmcnt(0)
	v_lshl_add_u64 v[4:5], v[4:5], 0, s[20:21]
	v_lshl_add_u64 v[6:7], v[6:7], 0, s[22:23]
	v_lshl_add_u64 v[6:7], v[6:7], 0, s[18:19]
	v_lshl_add_u64 v[4:5], v[4:5], 0, s[12:13]
	v_lshl_add_u64 v[6:7], v[6:7], 0, v[2:3]
	v_mov_b32_e32 v2, v3

.LBB0_283:
	s_waitcnt vmcnt(0)
	v_mov_b64_e32 v[2:3], s[0:1]
	global_load_dwordx2 v[4:5], v[2:3], off offset:16 sc0 sc1
	s_waitcnt vmcnt(0)
	global_load_dwordx2 v[6:7], v[2:3], off offset:24 sc0 sc1
	s_waitcnt vmcnt(0)
	global_load_dwordx2 v[8:9], v[2:3], off offset:72 sc0 sc1
	s_waitcnt vmcnt(0)
	s_and_b32 s4, s60, 0x7f
	s_mul_i32 s4, s4, 9
	s_lshr_b32 s8, s4, 1
	s_add_i32 s4, s4, 9
	s_ashr_i32 s2, s60, 7
	v_min_i32_e32 v16, 0xff, v0
	s_lshr_b32 s4, s4, 1
	s_add_i32 s3, s3, s8
	v_lshrrev_b32_e32 v22, 4, v16
	s_cmp_lt_u32 s3, s4
	s_movk_i32 s5, 0x200
	v_or_b32_e32 v22, 0x80, v22
	s_cselect_b64 s[12:13], -1, 0
	v_mov_b32_e32 v19, 0
	v_lshrrev_b32_e32 v27, 4, v0
	v_or_b32_e32 v13, 0x200, v0
	v_or_b32_e32 v14, 0x600, v0
	v_lshlrev_b32_e32 v16, 2, v16
	v_cmp_gt_u32_e32 vcc, s5, v0
	v_min_u32_e32 v22, 0x81, v22
	s_and_b64 s[4:5], s[12:13], exec
	v_mov_b32_e32 v24, 0x2400000
	v_lshlrev_b32_e32 v12, 4, v0
	v_lshlrev_b32_e32 v10, 12, v27
	v_lshrrev_b32_e32 v28, 4, v13
	v_lshrrev_b32_e32 v73, 4, v14
	v_mov_b32_e32 v23, v19
	v_and_b32_e32 v26, 60, v16
	v_lshlrev_b32_e32 v22, 12, v22
	s_cselect_b32 s3, s3, s8
	v_and_b32_e32 v72, 15, v0
	s_mov_b32 s19, 0
	v_mov_b32_e32 v11, v19
	v_and_b32_e32 v20, 0xf0, v12
	v_mov_b32_e32 v13, v19
	v_mov_b32_e32 v15, v19
	v_mov_b32_e32 v59, v19
	v_lshlrev_b32_e32 v12, 12, v28
	v_or_b32_e32 v14, 0x40000, v10
	v_or_b32_e32 v25, 0xffffff80, v73
	v_lshlrev_b32_e32 v58, 2, v26
	s_lshl_b32 s18, s3, 4
	v_lshrrev_b32_e32 v1, 4, v98
	s_mov_b32 s6, 0xfff80000
	v_lshlrev_b32_e32 v2, 2, v72
	v_mov_b32_e32 v3, v19
	v_cndmask_b32_e32 v16, v25, v73, vcc
	v_mul_u32_u24_e32 v18, 0x48000, v1
	s_mov_b32 s7, 0x9000
	s_mov_b32 s3, 0x12000
	v_mov_b32_e32 v21, v19
	v_mov_b32_e32 v17, v19
	v_lshlrev_b64 v[16:17], 12, v[16:17]
	s_waitcnt lgkmcnt(0)
	s_barrier
	v_and_b32_e32 v74, 0x78, v99
	v_lshl_add_u64 v[60:61], v[4:5], 0, v[22:23]
	v_lshl_add_u64 v[10:11], v[6:7], 0, v[10:11]
	v_mad_i64_i32 v[8:9], s[4:5], s2, v24, v[8:9]
	v_lshl_add_u64 v[12:13], v[6:7], 0, v[12:13]
	v_lshl_add_u64 v[14:15], v[6:7], 0, v[14:15]
	v_cndmask_b32_e32 v7, v5, v7, vcc
	v_cndmask_b32_e32 v6, v4, v6, vcc
	v_lshl_add_u64 v[4:5], s[18:19], 2, v[8:9]
	v_lshl_add_u64 v[24:25], v[60:61], 0, v[58:59]
	v_lshl_add_u64 v[30:31], v[4:5], 0, v[2:3]
	v_add_co_u32_e32 v2, vcc, s6, v24
	v_lshl_add_u64 v[70:71], v[30:31], 0, v[18:19]
	s_nop 0
	v_addc_co_u32_e32 v3, vcc, -1, v25, vcc
	v_add_co_u32_e32 v30, vcc, s7, v70
	v_lshl_add_u64 v[66:67], v[10:11], 0, v[20:21]
	s_nop 0
	v_addc_co_u32_e32 v31, vcc, 0, v71, vcc
	v_add_co_u32_e32 v32, vcc, s3, v70
	s_mov_b32 s3, 0x1b000
	s_nop 0
	v_addc_co_u32_e32 v33, vcc, 0, v71, vcc
	v_add_co_u32_e32 v34, vcc, s3, v70
	s_mov_b32 s3, 0x24000
	s_nop 0
	v_addc_co_u32_e32 v35, vcc, 0, v71, vcc
	v_lshl_add_u64 v[62:63], v[12:13], 0, v[20:21]
	v_lshl_add_u64 v[64:65], v[14:15], 0, v[20:21]
	v_lshl_add_u64 v[22:23], v[6:7], 0, v[16:17]
	global_load_dwordx4 v[14:17], v[66:67], off
	global_load_dwordx4 v[10:13], v[62:63], off
	global_load_dwordx4 v[6:9], v[64:65], off
	v_add_co_u32_e32 v36, vcc, s3, v70
	s_mov_b32 s3, 0x2d000
	s_nop 0
	v_addc_co_u32_e32 v37, vcc, 0, v71, vcc
	v_add_co_u32_e32 v38, vcc, s3, v70
	s_mov_b32 s3, 0x36000
	s_nop 0
	v_addc_co_u32_e32 v39, vcc, 0, v71, vcc
	v_add_co_u32_e32 v40, vcc, s3, v70
	s_mov_b32 s3, 0x3f000
	s_nop 0
	v_addc_co_u32_e32 v41, vcc, 0, v71, vcc
	v_add_co_u32_e32 v42, vcc, s3, v70
	s_mov_b32 s3, 0x120000
	s_nop 0
	v_addc_co_u32_e32 v43, vcc, 0, v71, vcc
	v_add_co_u32_e32 v44, vcc, s3, v70
	s_mov_b32 s3, 0x129000
	s_nop 0
	v_addc_co_u32_e32 v45, vcc, 0, v71, vcc
	v_lshl_add_u64 v[68:69], v[22:23], 0, v[20:21]
	global_load_dwordx4 v[2:5], v[2:3], off
	s_waitcnt vmcnt(3)
	v_mul_f32_e32 v29, 0xbfb8aa3b, v14
	global_load_dword v20, v[70:71], off
	global_load_dword v26, v[30:31], off
	global_load_dword v25, v[32:33], off
	global_load_dword v24, v[34:35], off
	global_load_dword v23, v[36:37], off
	global_load_dword v22, v[38:39], off
	global_load_dword v21, v[40:41], off
	global_load_dword v18, v[42:43], off
	global_load_dword v117, v[44:45], off
	v_add_co_u32_e32 v30, vcc, s3, v70
	s_mov_b32 s3, 0x132000
	s_nop 0
	v_addc_co_u32_e32 v31, vcc, 0, v71, vcc
	v_add_co_u32_e32 v32, vcc, s3, v70
	s_mov_b32 s3, 0x13b000
	s_nop 0
	v_addc_co_u32_e32 v33, vcc, 0, v71, vcc
	v_add_co_u32_e32 v34, vcc, s3, v70
	s_mov_b32 s3, 0x144000
	s_nop 0
	v_addc_co_u32_e32 v35, vcc, 0, v71, vcc
	v_add_co_u32_e32 v36, vcc, s3, v70
	s_mov_b32 s3, 0x14d000
	s_nop 0
	v_addc_co_u32_e32 v37, vcc, 0, v71, vcc
	v_add_co_u32_e32 v38, vcc, s3, v70
	s_mov_b32 s3, 0x156000
	s_nop 0
	v_addc_co_u32_e32 v39, vcc, 0, v71, vcc
	v_add_co_u32_e32 v40, vcc, s3, v70
	s_mov_b32 s3, 0x15f000
	s_nop 0
	v_addc_co_u32_e32 v41, vcc, 0, v71, vcc
	v_add_co_u32_e32 v42, vcc, s3, v70
	s_mov_b32 s3, 0x240000
	s_nop 0
	v_addc_co_u32_e32 v43, vcc, 0, v71, vcc
	v_add_co_u32_e32 v44, vcc, s3, v70
	s_mov_b32 s3, 0x249000
	s_nop 0
	v_addc_co_u32_e32 v45, vcc, 0, v71, vcc
	global_load_dword v135, v[30:31], off
	global_load_dword v132, v[32:33], off
	global_load_dword v129, v[34:35], off
	global_load_dword v126, v[36:37], off
	global_load_dword v123, v[38:39], off
	global_load_dword v120, v[40:41], off
	global_load_dword v113, v[42:43], off
	global_load_dword v85, v[44:45], off
	v_add_co_u32_e32 v30, vcc, s3, v70
	s_mov_b32 s3, 0x252000
	s_nop 0
	v_addc_co_u32_e32 v31, vcc, 0, v71, vcc
	v_add_co_u32_e32 v32, vcc, s3, v70
	s_mov_b32 s3, 0x25b000
	s_nop 0
	v_addc_co_u32_e32 v33, vcc, 0, v71, vcc
	v_add_co_u32_e32 v34, vcc, s3, v70
	s_mov_b32 s3, 0x264000
	s_nop 0
	v_addc_co_u32_e32 v35, vcc, 0, v71, vcc
	v_add_co_u32_e32 v36, vcc, s3, v70
	s_mov_b32 s3, 0x26d000
	s_nop 0
	v_addc_co_u32_e32 v37, vcc, 0, v71, vcc
	v_add_co_u32_e32 v38, vcc, s3, v70
	s_mov_b32 s3, 0x276000
	s_nop 0
	v_addc_co_u32_e32 v39, vcc, 0, v71, vcc
	v_add_co_u32_e32 v40, vcc, s3, v70
	s_mov_b32 s3, 0x27f000
	s_nop 0
	v_addc_co_u32_e32 v41, vcc, 0, v71, vcc
	v_add_co_u32_e32 v42, vcc, s3, v70
	s_mov_b32 s3, 0x360000
	s_nop 0
	v_addc_co_u32_e32 v43, vcc, 0, v71, vcc
	v_add_co_u32_e32 v44, vcc, s3, v70
	s_mov_b32 s3, 0x369000
	s_nop 0
	v_addc_co_u32_e32 v45, vcc, 0, v71, vcc
	global_load_dword v110, v[30:31], off
	global_load_dword v106, v[32:33], off
	global_load_dword v102, v[34:35], off
	global_load_dword v97, v[36:37], off
	global_load_dword v92, v[38:39], off
	global_load_dword v89, v[40:41], off
	global_load_dword v80, v[42:43], off
	global_load_dword v121, v[44:45], off
	v_add_co_u32_e32 v30, vcc, s3, v70
	s_mov_b32 s3, 0x372000
	s_nop 0
	v_addc_co_u32_e32 v31, vcc, 0, v71, vcc
	v_add_co_u32_e32 v32, vcc, s3, v70
	s_mov_b32 s3, 0x37b000
	s_nop 0
	v_addc_co_u32_e32 v33, vcc, 0, v71, vcc
	v_add_co_u32_e32 v34, vcc, s3, v70
	s_mov_b32 s3, 0x384000
	s_nop 0
	v_addc_co_u32_e32 v35, vcc, 0, v71, vcc
	v_add_co_u32_e32 v36, vcc, s3, v70
	s_mov_b32 s3, 0x38d000
	s_nop 0
	v_addc_co_u32_e32 v37, vcc, 0, v71, vcc
	v_add_co_u32_e32 v38, vcc, s3, v70
	s_mov_b32 s3, 0x396000
	s_nop 0
	v_addc_co_u32_e32 v39, vcc, 0, v71, vcc
	v_add_co_u32_e32 v40, vcc, s3, v70
	s_mov_b32 s3, 0x39f000
	s_nop 0
	v_addc_co_u32_e32 v41, vcc, 0, v71, vcc
	v_add_co_u32_e32 v42, vcc, s3, v70
	s_mov_b32 s3, 0x480000
	s_nop 0
	v_addc_co_u32_e32 v43, vcc, 0, v71, vcc
	v_add_co_u32_e32 v44, vcc, s3, v70
	s_mov_b32 s3, 0x489000
	s_nop 0
	v_addc_co_u32_e32 v45, vcc, 0, v71, vcc
	global_load_dword v137, v[30:31], off
	global_load_dword v136, v[32:33], off
	global_load_dword v133, v[34:35], off
	global_load_dword v130, v[36:37], off
	global_load_dword v127, v[38:39], off
	global_load_dword v125, v[40:41], off
	global_load_dword v118, v[42:43], off
	global_load_dword v86, v[44:45], off
	v_add_co_u32_e32 v30, vcc, s3, v70
	s_mov_b32 s3, 0x492000
	s_nop 0
	v_addc_co_u32_e32 v31, vcc, 0, v71, vcc
	v_add_co_u32_e32 v32, vcc, s3, v70
	s_mov_b32 s3, 0x49b000
	s_nop 0
	v_addc_co_u32_e32 v33, vcc, 0, v71, vcc
	v_add_co_u32_e32 v34, vcc, s3, v70
	s_mov_b32 s3, 0x4a4000
	s_nop 0
	v_addc_co_u32_e32 v35, vcc, 0, v71, vcc
	v_add_co_u32_e32 v36, vcc, s3, v70
	s_mov_b32 s3, 0x4ad000
	s_nop 0
	v_addc_co_u32_e32 v37, vcc, 0, v71, vcc
	v_add_co_u32_e32 v38, vcc, s3, v70
	s_mov_b32 s3, 0x4b6000
	s_nop 0
	v_addc_co_u32_e32 v39, vcc, 0, v71, vcc
	v_add_co_u32_e32 v40, vcc, s3, v70
	s_mov_b32 s3, 0x4bf000
	s_nop 0
	v_addc_co_u32_e32 v41, vcc, 0, v71, vcc
	v_add_co_u32_e32 v42, vcc, s3, v70
	s_mov_b32 s3, 0x5a0000
	s_nop 0
	v_addc_co_u32_e32 v43, vcc, 0, v71, vcc
	v_add_co_u32_e32 v44, vcc, s3, v70
	s_mov_b32 s3, 0x5a9000
	s_nop 0
	v_addc_co_u32_e32 v45, vcc, 0, v71, vcc
	global_load_dword v115, v[30:31], off
	global_load_dword v111, v[32:33], off
	global_load_dword v107, v[34:35], off
	global_load_dword v103, v[36:37], off
	global_load_dword v95, v[38:39], off
	global_load_dword v90, v[40:41], off
	global_load_dword v83, v[42:43], off
	global_load_dword v87, v[44:45], off
	v_add_co_u32_e32 v30, vcc, s3, v70
	s_mov_b32 s3, 0x5b2000
	s_nop 0
	v_addc_co_u32_e32 v31, vcc, 0, v71, vcc
	v_add_co_u32_e32 v32, vcc, s3, v70
	s_mov_b32 s3, 0x5bb000
	s_nop 0
	v_addc_co_u32_e32 v33, vcc, 0, v71, vcc
	v_add_co_u32_e32 v34, vcc, s3, v70
	s_mov_b32 s3, 0x5c4000
	s_nop 0
	v_addc_co_u32_e32 v35, vcc, 0, v71, vcc
	v_exp_f32_e32 v29, v29
	v_add_co_u32_e32 v36, vcc, s3, v70
	s_mov_b32 s3, 0x5cd000
	s_nop 0
	v_addc_co_u32_e32 v37, vcc, 0, v71, vcc
	v_add_co_u32_e32 v38, vcc, s3, v70
	s_mov_b32 s3, 0x5d6000
	s_nop 0
	v_addc_co_u32_e32 v39, vcc, 0, v71, vcc
	v_add_f32_e32 v29, 1.0, v29
	v_add_co_u32_e32 v40, vcc, s3, v70
	v_div_scale_f32 v44, s[4:5], v29, v29, v14
	s_nop 0
	v_addc_co_u32_e32 v41, vcc, 0, v71, vcc
	s_mov_b32 s3, 0x5df000
	v_rcp_f32_e32 v45, v44
	v_add_co_u32_e32 v42, vcc, s3, v70
	s_movk_i32 s3, 0x90
	s_nop 0
	v_addc_co_u32_e32 v43, vcc, 0, v71, vcc
	global_load_dword v112, v[30:31], off
	global_load_dword v108, v[32:33], off
	global_load_dword v104, v[34:35], off
	global_load_dword v100, v[36:37], off
	global_load_dword v93, v[38:39], off
	global_load_dword v91, v[40:41], off
	global_load_dword v81, v[42:43], off
	v_mul_f32_e32 v32, 0xbfb8aa3b, v15
	v_exp_f32_e32 v32, v32
	v_fma_f32 v30, -v44, v45, 1.0
	v_fmac_f32_e32 v45, v30, v45
	v_div_scale_f32 v30, vcc, v14, v29, v14
	v_mul_f32_e32 v31, v30, v45
	v_fma_f32 v33, -v44, v31, v30
	v_add_f32_e32 v32, 1.0, v32
	v_fmac_f32_e32 v31, v33, v45
	v_div_scale_f32 v33, s[4:5], v32, v32, v15
	v_rcp_f32_e32 v34, v33
	v_fma_f32 v30, -v44, v31, v30
	v_div_fmas_f32 v30, v30, v45, v31
	v_mul_f32_e32 v31, 0xbfb8aa3b, v16
	v_div_fixup_f32 v29, v30, v29, v14
	v_fma_f32 v14, -v33, v34, 1.0
	v_exp_f32_e32 v31, v31
	v_fmac_f32_e32 v34, v14, v34
	v_div_scale_f32 v14, vcc, v15, v32, v15
	v_mul_f32_e32 v30, v14, v34
	v_fma_f32 v35, -v33, v30, v14
	v_fmac_f32_e32 v30, v35, v34
	v_add_f32_e32 v31, 1.0, v31
	v_fma_f32 v14, -v33, v30, v14
	v_div_scale_f32 v33, s[4:5], v31, v31, v16
	v_rcp_f32_e32 v35, v33
	v_div_fmas_f32 v14, v14, v34, v30
	v_div_fixup_f32 v30, v14, v32, v15
	v_mul_f32_e32 v32, 0xbfb8aa3b, v17
	v_fma_f32 v14, -v33, v35, 1.0
	v_exp_f32_e32 v32, v32
	v_fmac_f32_e32 v35, v14, v35
	v_div_scale_f32 v14, vcc, v16, v31, v16
	v_mul_f32_e32 v15, v14, v35
	v_fma_f32 v34, -v33, v15, v14
	v_fmac_f32_e32 v15, v34, v35
	v_add_f32_e32 v32, 1.0, v32
	v_fma_f32 v14, -v33, v15, v14
	v_div_scale_f32 v33, s[4:5], v32, v32, v17
	v_rcp_f32_e32 v34, v33
	v_div_fmas_f32 v14, v14, v35, v15
	v_div_fixup_f32 v31, v14, v31, v16
	v_fma_f32 v14, -v33, v34, 1.0
	v_fmac_f32_e32 v34, v14, v34
	v_div_scale_f32 v14, vcc, v17, v32, v17
	v_mul_f32_e32 v15, v14, v34
	v_fma_f32 v16, -v33, v15, v14
	v_fmac_f32_e32 v15, v16, v34
	v_fma_f32 v14, -v33, v15, v14
	v_div_fmas_f32 v14, v14, v34, v15
	v_div_fixup_f32 v17, v14, v32, v17
	v_cvt_pk_bf16_f32 v14, v29, v30
	v_cvt_pk_bf16_f32 v15, v31, v17
	s_nop 0
	v_lshlrev_b32_e32 v16, 16, v14
	v_sub_f32_e32 v16, v29, v16
	v_and_b32_e32 v29, 0xffff0000, v14
	v_sub_f32_e32 v29, v30, v29
	v_cvt_pk_bf16_f32 v16, v16, v29
	v_lshlrev_b32_e32 v29, 16, v15
	v_and_b32_e32 v30, 0xffff0000, v15
	v_sub_f32_e32 v29, v31, v29
	v_sub_f32_e32 v17, v17, v30
	v_cvt_pk_bf16_f32 v17, v29, v17
	s_waitcnt vmcnt(50)
	v_mul_f32_e32 v29, 0xbfb8aa3b, v10
	v_exp_f32_e32 v29, v29
	v_mad_u32_u24 v30, v27, s3, 0
	v_add_u32_e32 v76, v30, v74
	ds_write_b64 v76, v[14:15]
	ds_write_b64 v76, v[16:17] offset:20736
	v_add_f32_e32 v29, 1.0, v29
	v_div_scale_f32 v31, s[4:5], v29, v29, v10
	v_rcp_f32_e32 v32, v31
	v_mul_f32_e32 v16, 0xbfb8aa3b, v11
	v_exp_f32_e32 v16, v16
	v_fma_f32 v14, -v31, v32, 1.0
	v_fmac_f32_e32 v32, v14, v32
	v_div_scale_f32 v14, vcc, v10, v29, v10
	v_mul_f32_e32 v15, v14, v32
	v_fma_f32 v17, -v31, v15, v14
	v_add_f32_e32 v16, 1.0, v16
	v_fmac_f32_e32 v15, v17, v32
	v_div_scale_f32 v17, s[4:5], v16, v16, v11
	v_fma_f32 v14, -v31, v15, v14
	v_rcp_f32_e32 v31, v17
	v_div_fmas_f32 v14, v14, v32, v15
	v_div_fixup_f32 v14, v14, v29, v10
	v_mul_f32_e32 v29, 0xbfb8aa3b, v12
	v_fma_f32 v10, -v17, v31, 1.0
	v_fmac_f32_e32 v31, v10, v31
	v_div_scale_f32 v10, vcc, v11, v16, v11
	v_exp_f32_e32 v29, v29
	v_mul_f32_e32 v15, v10, v31
	v_fma_f32 v32, -v17, v15, v10
	v_fmac_f32_e32 v15, v32, v31
	v_fma_f32 v10, -v17, v15, v10
	v_add_f32_e32 v17, 1.0, v29
	v_div_scale_f32 v29, s[4:5], v17, v17, v12
	v_rcp_f32_e32 v32, v29
	v_div_fmas_f32 v10, v10, v31, v15
	v_div_fixup_f32 v15, v10, v16, v11
	v_mul_f32_e32 v16, 0xbfb8aa3b, v13
	v_fma_f32 v10, -v29, v32, 1.0
	v_exp_f32_e32 v16, v16
	v_fmac_f32_e32 v32, v10, v32
	v_div_scale_f32 v10, vcc, v12, v17, v12
	v_mul_f32_e32 v11, v10, v32
	v_fma_f32 v31, -v29, v11, v10
	v_fmac_f32_e32 v11, v31, v32
	v_add_f32_e32 v16, 1.0, v16
	v_fma_f32 v10, -v29, v11, v10
	v_div_scale_f32 v29, s[4:5], v16, v16, v13
	v_rcp_f32_e32 v31, v29
	v_div_fmas_f32 v10, v10, v32, v11
	v_div_fixup_f32 v17, v10, v17, v12
	v_fma_f32 v10, -v29, v31, 1.0
	v_fmac_f32_e32 v31, v10, v31
	v_div_scale_f32 v10, vcc, v13, v16, v13
	v_mul_f32_e32 v11, v10, v31
	v_fma_f32 v12, -v29, v11, v10
	v_fmac_f32_e32 v11, v12, v31
	v_fma_f32 v10, -v29, v11, v10
	v_div_fmas_f32 v10, v10, v31, v11
	v_div_fixup_f32 v13, v10, v16, v13
	s_waitcnt vmcnt(49)
	v_mul_f32_e32 v16, 0xbfb8aa3b, v6
	v_exp_f32_e32 v16, v16
	v_cvt_pk_bf16_f32 v10, v14, v15
	v_cvt_pk_bf16_f32 v11, v17, v13
	s_nop 0
	v_lshlrev_b32_e32 v12, 16, v10
	v_sub_f32_e32 v12, v14, v12
	v_and_b32_e32 v14, 0xffff0000, v10
	v_sub_f32_e32 v14, v15, v14
	v_and_b32_e32 v15, 0xffff0000, v11
	v_cvt_pk_bf16_f32 v12, v12, v14
	v_lshlrev_b32_e32 v14, 16, v11
	v_sub_f32_e32 v13, v13, v15
	v_add_f32_e32 v15, 1.0, v16
	v_sub_f32_e32 v14, v17, v14
	v_div_scale_f32 v16, s[4:5], v15, v15, v6
	v_cvt_pk_bf16_f32 v13, v14, v13
	v_mad_u32_u24 v14, v28, s3, 0
	v_rcp_f32_e32 v17, v16
	v_add_u32_e32 v79, v14, v74
	ds_write_b64 v79, v[10:11]
	ds_write_b64 v79, v[12:13] offset:20736
	v_mul_f32_e32 v12, 0xbfb8aa3b, v7
	v_exp_f32_e32 v12, v12
	v_fma_f32 v10, -v16, v17, 1.0
	v_fmac_f32_e32 v17, v10, v17
	v_div_scale_f32 v10, vcc, v6, v15, v6
	v_mul_f32_e32 v11, v10, v17
	v_fma_f32 v13, -v16, v11, v10
	v_add_f32_e32 v12, 1.0, v12
	v_fmac_f32_e32 v11, v13, v17
	v_div_scale_f32 v13, s[4:5], v12, v12, v7
	v_rcp_f32_e32 v14, v13
	v_fma_f32 v10, -v16, v11, v10
	v_div_fmas_f32 v10, v10, v17, v11
	v_div_fixup_f32 v10, v10, v15, v6
	v_fma_f32 v6, -v13, v14, 1.0
	v_mul_f32_e32 v15, 0xbfb8aa3b, v8
	v_fmac_f32_e32 v14, v6, v14
	v_div_scale_f32 v6, vcc, v7, v12, v7
	v_exp_f32_e32 v15, v15
	v_mul_f32_e32 v11, v6, v14
	v_fma_f32 v16, -v13, v11, v6
	v_fmac_f32_e32 v11, v16, v14
	v_fma_f32 v6, -v13, v11, v6
	v_add_f32_e32 v13, 1.0, v15
	v_div_scale_f32 v15, s[4:5], v13, v13, v8
	v_rcp_f32_e32 v16, v15
	v_div_fmas_f32 v6, v6, v14, v11
	v_div_fixup_f32 v11, v6, v12, v7
	v_mul_f32_e32 v12, 0xbfb8aa3b, v9
	v_exp_f32_e32 v12, v12
	v_fma_f32 v6, -v15, v16, 1.0
	v_fmac_f32_e32 v16, v6, v16
	v_div_scale_f32 v6, vcc, v8, v13, v8
	v_mul_f32_e32 v7, v6, v16
	v_fma_f32 v14, -v15, v7, v6
	v_add_f32_e32 v12, 1.0, v12
	v_fmac_f32_e32 v7, v14, v16
	v_div_scale_f32 v14, s[4:5], v12, v12, v9
	v_fma_f32 v6, -v15, v7, v6
	v_rcp_f32_e32 v15, v14
	v_div_fmas_f32 v6, v6, v16, v7
	v_div_fixup_f32 v13, v6, v13, v8
	s_movk_i32 s3, 0x300
	v_fma_f32 v6, -v14, v15, 1.0
	v_fmac_f32_e32 v15, v6, v15
	v_div_scale_f32 v6, vcc, v9, v12, v9
	v_mul_f32_e32 v7, v6, v15
	v_fma_f32 v8, -v14, v7, v6
	v_fmac_f32_e32 v7, v8, v15
	v_fma_f32 v6, -v14, v7, v6
	v_div_fmas_f32 v6, v6, v15, v7
	v_div_fixup_f32 v9, v6, v12, v9
	v_cvt_pk_bf16_f32 v6, v10, v11
	v_cvt_pk_bf16_f32 v7, v13, v9
	v_cmp_gt_u32_e64 s[8:9], s3, v0
	v_lshlrev_b32_e32 v8, 16, v6
	v_sub_f32_e32 v8, v10, v8
	v_and_b32_e32 v10, 0xffff0000, v6
	v_sub_f32_e32 v10, v11, v10
	v_cvt_pk_bf16_f32 v8, v8, v10
	v_lshlrev_b32_e32 v10, 16, v7
	v_and_b32_e32 v11, 0xffff0000, v7
	v_sub_f32_e32 v10, v13, v10
	v_sub_f32_e32 v9, v9, v11
	v_cvt_pk_bf16_f32 v9, v10, v9
	v_add_u32_e32 v10, 0x2400, v30
	v_add_u32_e32 v78, v10, v74
	ds_write_b64 v78, v[6:7]
	ds_write_b64 v78, v[8:9] offset:20736
	s_and_saveexec_b64 s[10:11], s[8:9]
	s_cbranch_execz .LBB0_291
	global_load_dwordx4 v[6:9], v[68:69], off
	s_movk_i32 s3, 0x220
	v_cmp_gt_u32_e64 s[6:7], s3, v0
	s_and_saveexec_b64 s[20:21], s[6:7]
	s_cbranch_execz .LBB0_286
	s_waitcnt vmcnt(0)
	v_mul_f32_e32 v10, 0xbfb8aa3b, v6
	v_exp_f32_e32 v10, v10
	s_nop 0
	v_add_f32_e32 v10, 1.0, v10
	v_div_scale_f32 v11, s[4:5], v10, v10, v6
	v_rcp_f32_e32 v12, v11
	v_div_scale_f32 v13, vcc, v6, v10, v6
	v_fma_f32 v14, -v11, v12, 1.0
	v_fmac_f32_e32 v12, v14, v12
	v_mul_f32_e32 v14, v13, v12
	v_fma_f32 v15, -v11, v14, v13
	v_fmac_f32_e32 v14, v15, v12
	v_fma_f32 v11, -v11, v14, v13
	v_div_fmas_f32 v11, v11, v12, v14
	v_div_fixup_f32 v19, v11, v10, v6

.LBB0_668:
	s_and_b64 vcc, exec, s[6:7]
	s_barrier
	s_cbranch_vccnz .LBB0_672
	s_nop 4
	v_mov_b64_e32 v[4:5], s[0:1]
	s_waitcnt vmcnt(0)
	global_load_dwordx2 v[38:39], v[4:5], off offset:80 sc0 sc1
	s_waitcnt vmcnt(0)
	s_mul_i32 s4, s2, 0x492000
	s_mul_hi_i32 s3, s2, 0x492000
	v_or_b32_e32 v40, s18, v72
	v_mov_b32_e32 v41, 0
	v_mov_b32_e32 v44, 0x9000
	s_add_u32 s4, s94, s4
	v_lshlrev_b64 v[42:43], 2, v[40:41]
	s_addc_u32 s5, s95, s3
	v_mul_u32_u24_e32 v40, 0x24000, v1
	s_mov_b64 s[6:7], 0x5800000
	v_lshl_add_u64 v[4:5], s[4:5], 0, v[42:43]
	v_lshl_add_u64 v[4:5], v[4:5], 0, s[6:7]
	s_mov_b32 s9, 0x12000
	v_lshl_add_u64 v[40:41], v[4:5], 0, v[40:41]
	s_mov_b32 s10, 0x1b000
	s_mov_b32 s8, 0x24000
	s_mov_b32 s11, 0x2d000
	s_mov_b32 s12, 0xa2000
	s_mov_b32 s13, 0xab000
	s_mov_b32 s18, 0xb4000
	s_mov_b32 s19, 0xbd000
	s_mov_b32 s20, 0x132000
	s_mov_b32 s21, 0x13b000
	s_mov_b32 s22, 0x144000
	s_mov_b32 s23, 0x14d000
	s_mov_b32 s24, 0x1c2000
	s_mov_b32 s25, 0x1cb000
	s_mov_b32 s26, 0x1d4000
	s_mov_b32 s27, 0x1dd000
	s_mov_b32 s28, 0x252000
	s_mov_b32 s29, 0x25b000
	s_mov_b32 s30, 0x264000
	s_mov_b32 s31, 0x26d000
	s_mov_b32 s33, 0x2e2000
	s_waitcnt lgkmcnt(0)
	v_mad_i64_i32 v[38:39], s[2:3], s2, v44, v[38:39]
	v_lshl_add_u64 v[38:39], v[38:39], 0, v[42:43]
	global_load_dword v1, v[38:39], off
	v_add_co_u32_e32 v38, vcc, s9, v40
	s_mov_b32 s2, 0x2eb000
	s_nop 0
	v_addc_co_u32_e32 v39, vcc, 0, v41, vcc
	v_add_co_u32_e32 v42, vcc, s10, v40
	s_waitcnt vmcnt(0)
	v_add_f32_e32 v30, v30, v1
	v_addc_co_u32_e32 v43, vcc, 0, v41, vcc
	v_add_co_u32_e32 v44, vcc, s8, v40
	v_add_f32_e32 v14, v14, v1
	s_nop 0
	v_addc_co_u32_e32 v45, vcc, 0, v41, vcc
	v_add_co_u32_e32 v46, vcc, s11, v40
	v_add_f32_e32 v31, v31, v1
	s_nop 0
	v_addc_co_u32_e32 v47, vcc, 0, v41, vcc
	v_add_co_u32_e32 v48, vcc, s12, v40
	v_add_f32_e32 v32, v32, v1
	s_nop 0
	v_addc_co_u32_e32 v49, vcc, 0, v41, vcc
	v_add_co_u32_e32 v50, vcc, s13, v40
	v_add_f32_e32 v33, v33, v1
	s_nop 0
	v_addc_co_u32_e32 v51, vcc, 0, v41, vcc
	v_add_co_u32_e32 v52, vcc, s18, v40
	v_add_f32_e32 v15, v15, v1
	s_nop 0
	v_addc_co_u32_e32 v53, vcc, 0, v41, vcc
	v_add_co_u32_e32 v54, vcc, s19, v40
	v_add_f32_e32 v16, v16, v1
	s_nop 0
	v_addc_co_u32_e32 v55, vcc, 0, v41, vcc
	v_add_co_u32_e32 v56, vcc, s20, v40
	v_add_f32_e32 v17, v17, v1
	s_nop 0
	v_addc_co_u32_e32 v57, vcc, 0, v41, vcc
	v_add_co_u32_e32 v58, vcc, s21, v40
	v_add_f32_e32 v34, v34, v1
	s_nop 0
	v_addc_co_u32_e32 v59, vcc, 0, v41, vcc
	v_add_co_u32_e32 v60, vcc, s22, v40
	v_add_f32_e32 v35, v35, v1
	s_nop 0
	v_addc_co_u32_e32 v61, vcc, 0, v41, vcc
	v_add_co_u32_e32 v62, vcc, s23, v40
	v_add_f32_e32 v36, v36, v1
	s_nop 0
	v_addc_co_u32_e32 v63, vcc, 0, v41, vcc
	v_add_co_u32_e32 v64, vcc, s24, v40
	v_add_f32_e32 v37, v37, v1
	s_nop 0
	v_addc_co_u32_e32 v65, vcc, 0, v41, vcc
	v_add_co_u32_e32 v66, vcc, s25, v40
	v_add_f32_e32 v22, v22, v1
	s_nop 0
	v_addc_co_u32_e32 v67, vcc, 0, v41, vcc
	v_add_co_u32_e32 v68, vcc, s26, v40
	v_add_f32_e32 v23, v23, v1
	s_nop 0
	v_addc_co_u32_e32 v69, vcc, 0, v41, vcc
	v_add_co_u32_e32 v70, vcc, s27, v40
	v_add_f32_e32 v24, v24, v1
	s_nop 0
	v_addc_co_u32_e32 v71, vcc, 0, v41, vcc
	v_add_co_u32_e32 v72, vcc, s28, v40
	v_add_f32_e32 v25, v25, v1
	s_nop 0
	v_addc_co_u32_e32 v73, vcc, 0, v41, vcc
	v_add_co_u32_e32 v74, vcc, s29, v40
	v_add_f32_e32 v26, v26, v1
	s_nop 0
	v_addc_co_u32_e32 v75, vcc, 0, v41, vcc
	v_add_co_u32_e32 v76, vcc, s30, v40
	v_add_f32_e32 v27, v27, v1
	s_nop 0
	v_addc_co_u32_e32 v77, vcc, 0, v41, vcc
	v_add_co_u32_e32 v78, vcc, s31, v40
	v_add_f32_e32 v28, v28, v1
	s_nop 0
	v_addc_co_u32_e32 v79, vcc, 0, v41, vcc
	v_add_f32_e32 v29, v29, v1
	global_store_dword v[38:39], v30, off
	global_store_dword v[42:43], v31, off
	global_store_dword v[44:45], v32, off
	global_store_dword v[46:47], v33, off
	global_store_dword v[48:49], v14, off
	global_store_dword v[50:51], v15, off
	global_store_dword v[52:53], v16, off
	global_store_dword v[54:55], v17, off
	global_store_dword v[56:57], v34, off
	global_store_dword v[58:59], v35, off
	global_store_dword v[60:61], v36, off
	global_store_dword v[62:63], v37, off
	global_store_dword v[64:65], v22, off
	global_store_dword v[66:67], v23, off
	global_store_dword v[68:69], v24, off
	global_store_dword v[70:71], v25, off
	global_store_dword v[72:73], v26, off
	global_store_dword v[74:75], v27, off
	global_store_dword v[76:77], v28, off
	global_store_dword v[78:79], v29, off
	v_add_co_u32_e32 v14, vcc, s33, v40
	v_add_f32_e32 v10, v10, v1
	s_nop 0
	v_addc_co_u32_e32 v15, vcc, 0, v41, vcc
	global_store_dword v[14:15], v10, off
	v_add_co_u32_e32 v10, vcc, s2, v40
	v_add_f32_e32 v14, v11, v1
	s_nop 0
	v_addc_co_u32_e32 v11, vcc, 0, v41, vcc
	s_mov_b32 s2, 0x2f4000
	global_store_dword v[10:11], v14, off
	v_add_co_u32_e32 v10, vcc, s2, v40
	v_add_f32_e32 v12, v12, v1
	s_nop 0
	v_addc_co_u32_e32 v11, vcc, 0, v41, vcc
	s_mov_b32 s2, 0x2fd000
	global_store_dword v[10:11], v12, off
	v_add_co_u32_e32 v10, vcc, s2, v40
	v_add_f32_e32 v12, v13, v1
	s_nop 0
	v_addc_co_u32_e32 v11, vcc, 0, v41, vcc
	s_mov_b32 s2, 0x372000
	global_store_dword v[10:11], v12, off
	v_add_co_u32_e32 v10, vcc, s2, v40
	v_add_f32_e32 v12, v18, v1
	s_nop 0
	v_addc_co_u32_e32 v11, vcc, 0, v41, vcc
	s_mov_b32 s2, 0x37b000
	global_store_dword v[10:11], v12, off
	v_add_co_u32_e32 v10, vcc, s2, v40
	v_add_f32_e32 v12, v19, v1
	s_nop 0
	v_addc_co_u32_e32 v11, vcc, 0, v41, vcc
	s_mov_b32 s2, 0x384000
	global_store_dword v[10:11], v12, off
	v_add_co_u32_e32 v10, vcc, s2, v40
	v_add_f32_e32 v12, v20, v1
	s_nop 0
	v_addc_co_u32_e32 v11, vcc, 0, v41, vcc
	s_mov_b32 s2, 0x38d000
	global_store_dword v[10:11], v12, off
	v_add_co_u32_e32 v10, vcc, s2, v40
	v_add_f32_e32 v12, v21, v1
	s_nop 0
	v_addc_co_u32_e32 v11, vcc, 0, v41, vcc
	s_mov_b32 s2, 0x402000
	global_store_dword v[10:11], v12, off
	v_add_co_u32_e32 v10, vcc, s2, v40
	v_add_f32_e32 v6, v6, v1
	s_nop 0
	v_addc_co_u32_e32 v11, vcc, 0, v41, vcc
	s_mov_b32 s2, 0x40b000
	global_store_dword v[10:11], v6, off
	v_add_co_u32_e32 v6, vcc, s2, v40
	v_add_f32_e32 v10, v7, v1
	s_nop 0
	v_addc_co_u32_e32 v7, vcc, 0, v41, vcc
	s_mov_b32 s2, 0x414000
	global_store_dword v[6:7], v10, off
	v_add_co_u32_e32 v6, vcc, s2, v40
	v_add_f32_e32 v8, v8, v1
	s_nop 0
	v_addc_co_u32_e32 v7, vcc, 0, v41, vcc
	global_store_dword v[6:7], v8, off
	v_add_co_u32_e32 v6, vcc, 0x41d000, v40
	v_add_f32_e32 v8, v9, v1
	s_nop 0
	v_addc_co_u32_e32 v7, vcc, 0, v41, vcc
	v_cmp_gt_u32_e32 vcc, 16, v98
	global_store_dword v[6:7], v8, off
	s_and_saveexec_b64 s[6:7], vcc
	s_cbranch_execz .LBB0_671
	v_add_f32_e32 v2, v2, v1
	global_store_dword v[4:5], v2, off
	v_add_co_u32_e32 v2, vcc, 0x9000, v4
	v_add_f32_e32 v1, v3, v1
	s_nop 0
	v_addc_co_u32_e32 v3, vcc, 0, v5, vcc
	global_store_dword v[2:3], v1, off

.LBB0_727:
	v_mov_b32_e32 v130, v0
	s_mov_b64 s[38:39], s[94:95]
	s_mov_b64 s[4:5], s[92:93]
	s_mov_b32 s40, s60
	v_readfirstlane_b32 s2, v130
	v_writelane_b32 v228, s4, 4
	s_ashr_i32 s3, s2, 6
	s_mov_b32 s2, s60
	v_writelane_b32 v228, s5, 5
	v_writelane_b32 v228, s2, 6
	s_mov_b32 s96, 0
	v_and_b32_e32 v132, 63, v130
	v_writelane_b32 v228, s3, 7
	s_lshl_b32 s2, s40, 3
	s_add_i32 s12, s2, s3
	s_add_u32 s4, s38, 0x4000
	v_writelane_b32 v228, s4, 8
	s_addc_u32 s4, s39, 0
	v_writelane_b32 v228, s4, 10
	s_add_i32 s4, s96, 0x20160
	s_add_u32 s42, s38, 0x5800000
	s_addc_u32 s43, s39, 0
	s_cmp_lt_i32 s90, 2
	v_writelane_b32 v228, s4, 12
	s_cselect_b64 s[4:5], -1, 0
	s_cmp_gt_i32 s91, 1
	s_cselect_b64 s[6:7], -1, 0
	s_and_b64 s[4:5], s[4:5], s[6:7]
	s_load_dword s37, s[0:1], 0xe8
	s_andn2_b64 vcc, exec, s[4:5]
	s_waitcnt lgkmcnt(0)
	s_cbranch_vccnz .LBB0_789
	v_mov_b64_e32 v[2:3], s[0:1]
	global_load_dwordx2 v[2:3], v[2:3], off offset:88 sc0 sc1
	s_waitcnt vmcnt(0)
	s_cmpk_gt_i32 s12, 0x101f
	s_cbranch_scc1 .LBB0_735
	v_mov_b32_e32 v83, 0
	v_lshlrev_b32_e32 v4, 4, v132
	v_mov_b32_e32 v5, v83
	s_waitcnt lgkmcnt(0)
	v_lshl_add_u64 v[18:19], v[2:3], 0, v[4:5]
	global_load_dwordx4 v[2:5], v[18:19], off
	global_load_dwordx4 v[6:9], v[18:19], off offset:1024
	global_load_dwordx4 v[10:13], v[18:19], off offset:2048
	global_load_dwordx4 v[14:17], v[18:19], off offset:3072
	v_mbcnt_lo_u32_b32 v1, -1, 0
	v_mbcnt_hi_u32_b32 v18, -1, v1
	v_and_b32_e32 v1, 64, v18
	v_add_u32_e32 v19, 64, v1
	v_xor_b32_e32 v1, 1, v18
	v_cmp_lt_i32_e32 vcc, v1, v19
	v_xor_b32_e32 v20, 2, v18
	s_add_u32 s8, s0, 8
	v_cndmask_b32_e32 v1, v18, v1, vcc
	v_cmp_lt_i32_e32 vcc, v20, v19
	s_addc_u32 s9, s1, 0
	s_lshl_b32 s10, s12, 2
	v_cndmask_b32_e32 v20, v18, v20, vcc
	v_lshlrev_b32_e32 v97, 2, v20
	v_xor_b32_e32 v20, 4, v18
	v_cmp_lt_i32_e32 vcc, v20, v19
	s_lshl_b32 s16, s37, 5
	s_ashr_i32 s11, s10, 31
	v_cndmask_b32_e32 v20, v18, v20, vcc
	v_lshlrev_b32_e32 v98, 2, v20
	v_xor_b32_e32 v20, 8, v18
	v_cmp_lt_i32_e32 vcc, v20, v19
	v_lshlrev_b32_e32 v82, 3, v132
	s_ashr_i32 s17, s16, 31
	v_cndmask_b32_e32 v20, v18, v20, vcc
	v_lshlrev_b32_e32 v99, 2, v20
	v_xor_b32_e32 v20, 16, v18
	v_cmp_lt_i32_e32 vcc, v20, v19
	s_lshl_b64 s[6:7], s[10:11], 11
	s_mov_b64 s[4:5], 0xba00000
	v_cndmask_b32_e32 v20, v18, v20, vcc
	v_lshlrev_b32_e32 v100, 2, v20
	v_xor_b32_e32 v20, 32, v18
	v_cmp_lt_i32_e32 vcc, v20, v19
	s_add_u32 s6, s38, s6
	s_addc_u32 s7, s39, s7
	v_cndmask_b32_e32 v18, v18, v20, vcc
	v_lshlrev_b32_e32 v101, 2, v18
	v_lshl_add_u64 v[18:19], s[38:39], 0, v[82:83]
	v_lshl_add_u64 v[84:85], v[18:19], 0, s[4:5]
	v_lshlrev_b32_e32 v18, 2, v132
	v_or_b32_e32 v20, 0x100, v18
	v_or_b32_e32 v22, 0x200, v18
	v_or_b32_e32 v24, 0x300, v18
	v_lshl_add_u64 v[26:27], s[6:7], 0, v[82:83]
	s_lshl_b64 s[20:21], s[10:11], 12
	s_mov_b32 s15, 0
	v_lshlrev_b32_e32 v1, 2, v1
	v_lshl_add_u64 v[86:87], v[26:27], 0, s[4:5]
	s_lshl_b64 s[18:19], s[16:17], 11
	s_or_b32 s20, s20, 0x3000
	s_lshl_b64 s[22:23], s[16:17], 12
	v_lshlrev_b32_e32 v82, 4, v132
	v_mov_b32_e32 v102, 0x358637bd
	s_mov_b32 s4, 0xf800000
	v_mov_b32_e32 v103, 0x260
	v_lshlrev_b32_e32 v88, 2, v18
	s_movk_i32 s5, 0x7fff
	s_mov_b32 s13, 0xffff0000
	v_lshlrev_b32_e32 v90, 2, v20
	v_lshlrev_b32_e32 v92, 2, v22
	v_lshlrev_b32_e32 v94, 2, v24
	s_movk_i32 s26, 0x1000
	s_branch .LBB0_731
.LBB0_730:
	v_pk_mul_f32 v[24:25], v[80:81], v[80:81]
	v_pk_mul_f32 v[26:27], v[78:79], v[78:79]
	s_ashr_i32 s27, s10, 13
	v_pk_mov_b32 v[28:29], v[26:27], v[24:25] op_sel:[1,0]
	v_mov_b32_e32 v27, v25
	v_pk_add_f32 v[24:25], v[28:29], v[26:27]
	v_pk_mul_f32 v[26:27], v[76:77], v[76:77]
	v_pk_mul_f32 v[28:29], v[74:75], v[74:75]
	s_and_b64 s[6:7], s[6:7], exec
	v_pk_mov_b32 v[34:35], v[28:29], v[26:27] op_sel:[1,0]
	v_mov_b32_e32 v29, v27
	v_pk_add_f32 v[26:27], v[34:35], v[28:29]
	v_mul_f32_e32 v28, v66, v66
	v_mul_f32_e32 v29, v67, v67
	v_pk_add_f32 v[24:25], v[24:25], v[24:25] op_sel:[0,1] op_sel_hi:[1,0]
	v_pk_add_f32 v[26:27], v[26:27], v[26:27] op_sel:[0,1] op_sel_hi:[1,0]
	s_cselect_b32 s6, s27, s28
	v_mov_b32_e32 v25, v28
	v_mov_b32_e32 v27, v29
	s_mul_hi_i32 s7, s6, 0x9000
	s_mul_i32 s6, s6, 0x9000
	v_pk_add_f32 v[24:25], v[24:25], v[26:27]
	v_mul_f32_e32 v26, v71, v71
	v_mul_f32_e32 v28, v73, v73
	s_add_u32 s6, s42, s6
	v_mul_f32_e32 v34, v68, v68
	v_mul_f32_e32 v35, v69, v69
	v_pk_fma_f32 v[26:27], v[70:71], v[70:71], v[26:27] op_sel_hi:[1,1,0]
	v_pk_fma_f32 v[28:29], v[72:73], v[72:73], v[28:29] op_sel_hi:[1,1,0]
	s_addc_u32 s7, s43, s7
	v_mov_b32_e32 v27, v34
	v_mov_b32_e32 v29, v35
	s_add_u32 s50, s6, 0x1000
	v_mov_b32_e32 v89, v83
	v_pk_add_f32 v[26:27], v[26:27], v[28:29]
	s_addc_u32 s51, s7, 0
	v_lshl_add_u64 v[112:113], s[6:7], 0, v[88:89]
	v_pk_add_f32 v[24:25], v[24:25], v[26:27]
	v_lshl_add_u64 v[26:27], s[50:51], 0, v[88:89]
	global_load_dwordx4 v[104:107], v[112:113], off
	global_load_dwordx4 v[108:111], v[26:27], off
	v_add_f32_e32 v24, v24, v25
	ds_bpermute_b32 v25, v1, v24
	v_lshl_add_u64 v[22:23], v[22:23], 0, v[82:83]
	v_mul_f32_e32 v116, v53, v53
	s_waitcnt lgkmcnt(0)
	v_add_f32_e32 v24, v24, v25
	ds_bpermute_b32 v25, v97, v24
	s_waitcnt lgkmcnt(0)
	v_add_f32_e32 v24, v24, v25
	ds_bpermute_b32 v25, v98, v24
	s_waitcnt lgkmcnt(0)
	v_add_f32_e32 v24, v24, v25
	ds_bpermute_b32 v25, v99, v24
	s_waitcnt lgkmcnt(0)
	v_add_f32_e32 v24, v24, v25
	ds_bpermute_b32 v25, v100, v24
	s_waitcnt lgkmcnt(0)
	v_add_f32_e32 v24, v24, v25
	ds_bpermute_b32 v25, v101, v24
	s_waitcnt lgkmcnt(0)
	v_add_f32_e32 v24, v24, v25
	v_fmamk_f32 v24, v24, 0x3a800000, v102
	v_mul_f32_e32 v25, 0x4f800000, v24
	v_cmp_gt_f32_e32 vcc, s4, v24
	s_waitcnt vmcnt(0)
	v_pk_add_f32 v[108:109], v[108:109], 1.0 op_sel_hi:[1,0]
	v_cndmask_b32_e32 v24, v24, v25, vcc
	v_sqrt_f32_e32 v25, v24
	v_pk_add_f32 v[110:111], v[110:111], 1.0 op_sel_hi:[1,0]
	v_add_u32_e32 v26, -1, v25
	v_fma_f32 v27, -v26, v25, v24
	v_cmp_ge_f32_e64 s[6:7], 0, v27
	v_add_u32_e32 v27, 1, v25
	s_nop 0
	v_cndmask_b32_e64 v26, v25, v26, s[6:7]
	v_fma_f32 v25, -v27, v25, v24
	v_cmp_lt_f32_e64 s[6:7], 0, v25
	s_nop 1
	v_cndmask_b32_e64 v25, v26, v27, s[6:7]
	v_mul_f32_e32 v26, 0x37800000, v25
	v_cndmask_b32_e32 v25, v25, v26, vcc
	v_cmp_class_f32_e32 vcc, v24, v103
	s_and_b64 s[6:7], s[48:49], exec
	s_nop 0
	v_cndmask_b32_e32 v91, v25, v24, vcc
	v_div_scale_f32 v93, s[6:7], v91, v91, 1.0
	v_rcp_f32_e32 v95, v93
	global_load_dwordx4 v[42:45], v[22:23], off
	global_load_dwordx4 v[34:37], v[22:23], off offset:1024
	global_load_dwordx4 v[26:29], v[22:23], off offset:2048
	s_nop 0
	global_load_dwordx4 v[22:25], v[22:23], off offset:3072
	s_cselect_b32 s6, s27, s14
	s_mul_hi_i32 s7, s6, 0x9000
	v_fma_f32 v96, -v93, v95, 1.0
	v_fmac_f32_e32 v95, v96, v95
	v_div_scale_f32 v96, vcc, 1.0, v91, 1.0
	v_mul_f32_e32 v114, v96, v95
	v_fma_f32 v115, -v93, v114, v96
	v_fmac_f32_e32 v114, v115, v95
	v_fma_f32 v93, -v93, v114, v96
	v_div_fmas_f32 v93, v93, v95, v114
	v_div_fixup_f32 v96, v93, v91, 1.0
	v_pk_mul_f32 v[78:79], v[78:79], v[96:97] op_sel_hi:[1,0]
	v_pk_mul_f32 v[80:81], v[80:81], v[96:97] op_sel_hi:[1,0]
	v_pk_mul_f32 v[78:79], v[2:3], v[78:79]
	v_pk_mul_f32 v[80:81], v[4:5], v[80:81]
	v_pk_fma_f32 v[78:79], v[108:109], v[78:79], v[104:105]
	v_pk_fma_f32 v[80:81], v[110:111], v[80:81], v[106:107]
	v_bfe_u32 v91, v78, 16, 1
	v_add3_u32 v78, v78, v91, s5
	v_bfe_u32 v91, v79, 16, 1
	v_lshrrev_b32_e32 v78, 16, v78
	v_add3_u32 v79, v79, v91, s5
	v_and_or_b32 v78, v79, s13, v78
	v_bfe_u32 v79, v80, 16, 1
	v_add3_u32 v79, v80, v79, s5
	v_bfe_u32 v80, v81, 16, 1
	v_lshrrev_b32_e32 v79, 16, v79
	v_add3_u32 v80, v81, v80, s5
	v_and_or_b32 v79, v80, s13, v79
	v_mov_b32_e32 v91, v83
	global_store_dwordx2 v[86:87], v[78:79], off
	v_lshl_add_u64 v[78:79], s[50:51], 0, v[90:91]
	global_load_dwordx4 v[78:81], v[78:79], off
	s_nop 0
	global_load_dwordx4 v[104:107], v[112:113], off offset:1024
	v_pk_mul_f32 v[76:77], v[76:77], v[96:97] op_sel_hi:[1,0]
	v_pk_mul_f32 v[74:75], v[74:75], v[96:97] op_sel_hi:[1,0]
	v_pk_mul_f32 v[76:77], v[8:9], v[76:77]
	v_pk_mul_f32 v[74:75], v[6:7], v[74:75]
	v_mov_b32_e32 v93, v83
	v_lshl_add_u64 v[108:109], s[50:51], 0, v[92:93]
	v_pk_mul_f32 v[72:73], v[72:73], v[96:97] op_sel_hi:[1,0]
	v_pk_mul_f32 v[70:71], v[70:71], v[96:97] op_sel_hi:[1,0]
	v_pk_mul_f32 v[72:73], v[12:13], v[72:73]
	v_pk_mul_f32 v[70:71], v[10:11], v[70:71]
	v_mov_b32_e32 v95, v83
	v_pk_mul_f32 v[68:69], v[68:69], v[96:97] op_sel_hi:[1,0]
	v_pk_mul_f32 v[66:67], v[66:67], v[96:97] op_sel_hi:[1,0]
	v_pk_mul_f32 v[68:69], v[68:69], v[16:17]
	v_pk_mul_f32 v[66:67], v[66:67], v[14:15]
	s_mul_i32 s6, s6, 0x9000
	s_add_u32 s6, s42, s6
	v_mul_f32_e32 v111, v50, v50
	v_mul_f32_e32 v110, v57, v57
	s_addc_u32 s7, s43, s7
	v_mul_f32_e32 v115, v52, v52
	s_add_u32 s48, s6, 0x1000
	s_addc_u32 s49, s7, 0
	v_mul_f32_e32 v114, v51, v51
	s_add_i32 s14, s10, 0xffffc004
	s_waitcnt vmcnt(0) lgkmcnt(0)
	v_pk_add_f32 v[80:81], v[80:81], 1.0 op_sel_hi:[1,0]
	v_pk_add_f32 v[78:79], v[78:79], 1.0 op_sel_hi:[1,0]
	v_pk_fma_f32 v[76:77], v[80:81], v[76:77], v[106:107]
	v_pk_fma_f32 v[74:75], v[78:79], v[74:75], v[104:105]
	v_bfe_u32 v80, v76, 16, 1
	v_bfe_u32 v78, v74, 16, 1
	v_bfe_u32 v79, v75, 16, 1
	v_bfe_u32 v81, v77, 16, 1
	v_add3_u32 v74, v74, v78, s5
	v_add3_u32 v76, v76, v80, s5
	v_add3_u32 v75, v75, v79, s5
	v_add3_u32 v77, v77, v81, s5
	v_lshrrev_b32_e32 v74, 16, v74
	v_lshrrev_b32_e32 v76, 16, v76
	v_and_or_b32 v74, v75, s13, v74
	v_and_or_b32 v75, v77, s13, v76
	global_store_dwordx2 v[86:87], v[74:75], off offset:512
	global_load_dwordx4 v[74:77], v[108:109], off
	s_nop 0
	global_load_dwordx4 v[78:81], v[112:113], off offset:2048
	v_lshl_add_u64 v[104:105], s[50:51], 0, v[94:95]
	v_pk_mul_f32 v[106:107], v[58:59], v[58:59]
	v_mul_f32_e32 v108, v55, v55
	s_waitcnt vmcnt(0) lgkmcnt(0)
	v_pk_add_f32 v[76:77], v[76:77], 1.0 op_sel_hi:[1,0]
	v_pk_add_f32 v[74:75], v[74:75], 1.0 op_sel_hi:[1,0]
	v_pk_fma_f32 v[72:73], v[72:73], v[76:77], v[80:81]
	v_pk_fma_f32 v[70:71], v[70:71], v[74:75], v[78:79]
	v_bfe_u32 v76, v72, 16, 1
	v_bfe_u32 v74, v70, 16, 1
	v_bfe_u32 v75, v71, 16, 1
	v_bfe_u32 v77, v73, 16, 1
	v_add3_u32 v70, v70, v74, s5
	v_add3_u32 v72, v72, v76, s5
	v_add3_u32 v71, v71, v75, s5
	v_add3_u32 v73, v73, v77, s5
	v_lshrrev_b32_e32 v70, 16, v70
	v_lshrrev_b32_e32 v72, 16, v72
	v_and_or_b32 v70, v71, s13, v70
	v_and_or_b32 v71, v73, s13, v72
	global_store_dwordx2 v[86:87], v[70:71], off offset:1024
	global_load_dwordx4 v[70:73], v[104:105], off
	s_nop 0
	global_load_dwordx4 v[74:77], v[112:113], off offset:3072
	v_pk_mul_f32 v[78:79], v[64:65], v[64:65]
	v_pk_mul_f32 v[80:81], v[62:63], v[62:63]
	v_pk_mul_f32 v[104:105], v[60:61], v[60:61]
	v_pk_mov_b32 v[112:113], v[80:81], v[78:79] op_sel:[1,0]
	v_mov_b32_e32 v81, v79
	v_pk_mov_b32 v[78:79], v[106:107], v[104:105] op_sel:[1,0]
	v_mov_b32_e32 v107, v105
	v_pk_fma_f32 v[104:105], v[54:55], v[54:55], v[108:109] op_sel_hi:[1,1,0]
	v_pk_fma_f32 v[108:109], v[56:57], v[56:57], v[110:111] op_sel_hi:[1,1,0]
	v_pk_add_f32 v[78:79], v[78:79], v[106:107]
	v_mov_b32_e32 v105, v115
	v_mov_b32_e32 v109, v116
	v_lshl_add_u64 v[106:107], s[6:7], 0, v[88:89]
	v_pk_add_f32 v[104:105], v[104:105], v[108:109]
	v_lshl_add_u64 v[108:109], s[48:49], 0, v[88:89]
	v_pk_add_f32 v[80:81], v[112:113], v[80:81]
	v_pk_add_f32 v[78:79], v[78:79], v[78:79] op_sel:[0,1] op_sel_hi:[1,0]
	v_pk_add_f32 v[80:81], v[80:81], v[80:81] op_sel:[0,1] op_sel_hi:[1,0]
	v_mov_b32_e32 v79, v114
	v_mov_b32_e32 v81, v111
	s_waitcnt vmcnt(0) lgkmcnt(0)
	v_pk_add_f32 v[72:73], v[72:73], 1.0 op_sel_hi:[1,0]
	v_pk_add_f32 v[70:71], v[70:71], 1.0 op_sel_hi:[1,0]
	v_pk_fma_f32 v[68:69], v[68:69], v[72:73], v[76:77]
	v_pk_fma_f32 v[66:67], v[66:67], v[70:71], v[74:75]
	v_bfe_u32 v72, v68, 16, 1
	v_bfe_u32 v70, v66, 16, 1
	v_bfe_u32 v71, v67, 16, 1
	v_bfe_u32 v73, v69, 16, 1
	v_add3_u32 v66, v66, v70, s5
	v_add3_u32 v68, v68, v72, s5
	v_add3_u32 v67, v67, v71, s5
	v_add3_u32 v69, v69, v73, s5
	v_lshrrev_b32_e32 v66, 16, v66
	v_lshrrev_b32_e32 v68, 16, v68
	v_and_or_b32 v66, v67, s13, v66
	v_and_or_b32 v67, v69, s13, v68
	global_store_dwordx2 v[86:87], v[66:67], off offset:1536
	global_load_dwordx4 v[66:69], v[106:107], off
	s_nop 0
	global_load_dwordx4 v[70:73], v[108:109], off
	v_pk_add_f32 v[74:75], v[80:81], v[78:79]
	s_waitcnt vmcnt(0) lgkmcnt(0)
	v_pk_add_f32 v[72:73], v[72:73], 1.0 op_sel_hi:[1,0]
	v_pk_add_f32 v[74:75], v[74:75], v[104:105]
	v_pk_add_f32 v[70:71], v[70:71], 1.0 op_sel_hi:[1,0]
	v_add_f32_e32 v74, v74, v75
	ds_bpermute_b32 v75, v1, v74
	s_waitcnt lgkmcnt(0)
	v_add_f32_e32 v74, v74, v75
	ds_bpermute_b32 v75, v97, v74
	s_waitcnt lgkmcnt(0)
	v_add_f32_e32 v74, v74, v75
	ds_bpermute_b32 v75, v98, v74
	s_waitcnt lgkmcnt(0)
	v_add_f32_e32 v74, v74, v75
	ds_bpermute_b32 v75, v99, v74
	s_waitcnt lgkmcnt(0)
	v_add_f32_e32 v74, v74, v75
	ds_bpermute_b32 v75, v100, v74
	s_waitcnt lgkmcnt(0)
	v_add_f32_e32 v74, v74, v75
	ds_bpermute_b32 v75, v101, v74
	s_waitcnt lgkmcnt(0)
	v_add_f32_e32 v74, v74, v75
	v_fmamk_f32 v74, v74, 0x3a800000, v102
	v_mul_f32_e32 v75, 0x4f800000, v74
	v_cmp_gt_f32_e32 vcc, s4, v74
	s_nop 1
	v_cndmask_b32_e32 v74, v74, v75, vcc
	v_sqrt_f32_e32 v75, v74
	s_nop 0
	v_add_u32_e32 v76, -1, v75
	v_add_u32_e32 v77, 1, v75
	v_fma_f32 v78, -v76, v75, v74
	v_fma_f32 v79, -v77, v75, v74
	v_cmp_ge_f32_e64 s[6:7], 0, v78
	s_nop 1
	v_cndmask_b32_e64 v75, v75, v76, s[6:7]
	v_cmp_lt_f32_e64 s[6:7], 0, v79
	s_nop 1
	v_cndmask_b32_e64 v75, v75, v77, s[6:7]
	v_mul_f32_e32 v76, 0x37800000, v75
	v_cndmask_b32_e32 v75, v75, v76, vcc
	v_cmp_class_f32_e32 vcc, v74, v103
	s_and_b64 s[6:7], s[46:47], exec
	s_nop 0
	v_cndmask_b32_e32 v76, v75, v74, vcc
	v_div_scale_f32 v77, s[6:7], v76, v76, 1.0
	v_rcp_f32_e32 v78, v77
	v_div_scale_f32 v79, vcc, 1.0, v76, 1.0
	v_lshl_add_u64 v[74:75], s[48:49], 0, v[90:91]
	v_fma_f32 v80, -v77, v78, 1.0
	v_fmac_f32_e32 v78, v80, v78
	v_mul_f32_e32 v80, v79, v78
	v_fma_f32 v81, -v77, v80, v79
	v_fmac_f32_e32 v80, v81, v78
	v_fma_f32 v77, -v77, v80, v79
	v_div_fmas_f32 v77, v77, v78, v80
	v_div_fixup_f32 v76, v77, v76, 1.0
	v_pk_mul_f32 v[64:65], v[64:65], v[76:77] op_sel_hi:[1,0]
	v_pk_mul_f32 v[62:63], v[62:63], v[76:77] op_sel_hi:[1,0]
	v_pk_mul_f32 v[64:65], v[4:5], v[64:65]
	v_pk_mul_f32 v[62:63], v[2:3], v[62:63]
	v_pk_fma_f32 v[64:65], v[72:73], v[64:65], v[68:69]
	v_pk_fma_f32 v[62:63], v[70:71], v[62:63], v[66:67]
	v_bfe_u32 v68, v64, 16, 1
	v_bfe_u32 v66, v62, 16, 1
	v_bfe_u32 v67, v63, 16, 1
	v_bfe_u32 v69, v65, 16, 1
	v_add3_u32 v62, v62, v66, s5
	v_add3_u32 v64, v64, v68, s5
	v_add3_u32 v63, v63, v67, s5
	v_add3_u32 v65, v65, v69, s5
	v_lshrrev_b32_e32 v62, 16, v62
	v_lshrrev_b32_e32 v64, 16, v64
	v_and_or_b32 v62, v63, s13, v62
	v_and_or_b32 v63, v65, s13, v64
	global_store_dwordx2 v[86:87], v[62:63], off offset:2048
	global_load_dwordx4 v[62:65], v[74:75], off
	s_nop 0
	global_load_dwordx4 v[66:69], v[106:107], off offset:1024
	v_pk_mul_f32 v[60:61], v[60:61], v[76:77] op_sel_hi:[1,0]
	v_pk_mul_f32 v[58:59], v[58:59], v[76:77] op_sel_hi:[1,0]
	v_pk_mul_f32 v[60:61], v[8:9], v[60:61]
	v_pk_mul_f32 v[58:59], v[6:7], v[58:59]
	v_lshl_add_u64 v[70:71], s[48:49], 0, v[92:93]
	v_pk_mul_f32 v[56:57], v[56:57], v[76:77] op_sel_hi:[1,0]
	v_pk_mul_f32 v[54:55], v[54:55], v[76:77] op_sel_hi:[1,0]
	v_pk_mul_f32 v[56:57], v[12:13], v[56:57]
	v_pk_mul_f32 v[54:55], v[10:11], v[54:55]
	v_mul_f32_e32 v77, v19, v19
	v_pk_mul_f32 v[52:53], v[52:53], v[76:77] op_sel_hi:[1,0]
	v_pk_mul_f32 v[50:51], v[50:51], v[76:77] op_sel_hi:[1,0]
	v_pk_mul_f32 v[52:53], v[16:17], v[52:53]
	v_pk_mul_f32 v[50:51], v[14:15], v[50:51]
	s_cselect_b32 s6, s27, s14
	s_mul_hi_i32 s7, s6, 0x9000
	s_mul_i32 s6, s6, 0x9000
	s_add_u32 s6, s42, s6
	v_mul_f32_e32 v73, v18, v18
	v_mul_f32_e32 v72, v33, v33
	s_addc_u32 s7, s43, s7
	v_mul_f32_e32 v78, v20, v20
	v_mul_f32_e32 v79, v21, v21
	s_add_u32 s46, s6, 0x1000
	s_addc_u32 s47, s7, 0
	s_add_i32 s14, s10, 0xffffc005
	s_waitcnt vmcnt(0) lgkmcnt(0)
	v_pk_add_f32 v[64:65], v[64:65], 1.0 op_sel_hi:[1,0]
	v_pk_add_f32 v[62:63], v[62:63], 1.0 op_sel_hi:[1,0]
	v_pk_fma_f32 v[60:61], v[64:65], v[60:61], v[68:69]
	v_pk_fma_f32 v[58:59], v[62:63], v[58:59], v[66:67]
	v_bfe_u32 v64, v60, 16, 1
	v_bfe_u32 v62, v58, 16, 1
	v_bfe_u32 v63, v59, 16, 1
	v_bfe_u32 v65, v61, 16, 1
	v_add3_u32 v58, v58, v62, s5
	v_add3_u32 v60, v60, v64, s5
	v_add3_u32 v59, v59, v63, s5
	v_add3_u32 v61, v61, v65, s5
	v_lshrrev_b32_e32 v58, 16, v58
	v_lshrrev_b32_e32 v60, 16, v60
	v_and_or_b32 v58, v59, s13, v58
	v_and_or_b32 v59, v61, s13, v60
	global_store_dwordx2 v[86:87], v[58:59], off offset:2560
	global_load_dwordx4 v[58:61], v[70:71], off
	s_nop 0
	global_load_dwordx4 v[62:65], v[106:107], off offset:2048
	v_lshl_add_u64 v[66:67], s[48:49], 0, v[94:95]
	v_pk_mul_f32 v[68:69], v[38:39], v[38:39]
	v_mul_f32_e32 v70, v31, v31
	s_waitcnt vmcnt(0) lgkmcnt(0)
	v_pk_add_f32 v[60:61], v[60:61], 1.0 op_sel_hi:[1,0]
	v_pk_add_f32 v[58:59], v[58:59], 1.0 op_sel_hi:[1,0]
	v_pk_fma_f32 v[56:57], v[60:61], v[56:57], v[64:65]
	v_pk_fma_f32 v[54:55], v[58:59], v[54:55], v[62:63]
	v_bfe_u32 v60, v56, 16, 1
	v_bfe_u32 v58, v54, 16, 1
	v_bfe_u32 v59, v55, 16, 1
	v_bfe_u32 v61, v57, 16, 1
	v_add3_u32 v54, v54, v58, s5
	v_add3_u32 v56, v56, v60, s5
	v_add3_u32 v55, v55, v59, s5
	v_add3_u32 v57, v57, v61, s5
	v_lshrrev_b32_e32 v54, 16, v54
	v_lshrrev_b32_e32 v56, 16, v56
	v_and_or_b32 v54, v55, s13, v54
	v_and_or_b32 v55, v57, s13, v56
	global_store_dwordx2 v[86:87], v[54:55], off offset:3072
	global_load_dwordx4 v[54:57], v[66:67], off
	s_nop 0
	global_load_dwordx4 v[58:61], v[106:107], off offset:3072
	v_pk_mul_f32 v[62:63], v[48:49], v[48:49]
	v_pk_mul_f32 v[64:65], v[46:47], v[46:47]
	v_pk_mul_f32 v[66:67], v[40:41], v[40:41]
	v_pk_mov_b32 v[74:75], v[64:65], v[62:63] op_sel:[1,0]
	v_mov_b32_e32 v65, v63
	v_pk_mov_b32 v[62:63], v[68:69], v[66:67] op_sel:[1,0]
	v_mov_b32_e32 v69, v67
	v_pk_fma_f32 v[66:67], v[30:31], v[30:31], v[70:71] op_sel_hi:[1,1,0]
	v_pk_fma_f32 v[70:71], v[32:33], v[32:33], v[72:73] op_sel_hi:[1,1,0]
	v_pk_add_f32 v[62:63], v[62:63], v[68:69]
	v_mov_b32_e32 v67, v78
	v_mov_b32_e32 v71, v79
	v_lshl_add_u64 v[68:69], s[6:7], 0, v[88:89]
	v_pk_add_f32 v[66:67], v[66:67], v[70:71]
	v_lshl_add_u64 v[70:71], s[46:47], 0, v[88:89]
	v_pk_add_f32 v[64:65], v[74:75], v[64:65]
	v_pk_add_f32 v[62:63], v[62:63], v[62:63] op_sel:[0,1] op_sel_hi:[1,0]
	v_pk_add_f32 v[64:65], v[64:65], v[64:65] op_sel:[0,1] op_sel_hi:[1,0]
	v_mov_b32_e32 v63, v77
	v_mov_b32_e32 v65, v73
	s_waitcnt vmcnt(0) lgkmcnt(0)
	v_pk_add_f32 v[56:57], v[56:57], 1.0 op_sel_hi:[1,0]
	v_pk_add_f32 v[54:55], v[54:55], 1.0 op_sel_hi:[1,0]
	v_pk_fma_f32 v[52:53], v[52:53], v[56:57], v[60:61]
	v_pk_fma_f32 v[50:51], v[50:51], v[54:55], v[58:59]
	v_bfe_u32 v56, v52, 16, 1
	v_bfe_u32 v54, v50, 16, 1
	v_bfe_u32 v55, v51, 16, 1
	v_bfe_u32 v57, v53, 16, 1
	v_add3_u32 v50, v50, v54, s5
	v_add3_u32 v52, v52, v56, s5
	v_add3_u32 v51, v51, v55, s5
	v_add3_u32 v53, v53, v57, s5
	v_lshrrev_b32_e32 v50, 16, v50
	v_lshrrev_b32_e32 v52, 16, v52
	v_and_or_b32 v50, v51, s13, v50
	v_and_or_b32 v51, v53, s13, v52
	global_store_dwordx2 v[86:87], v[50:51], off offset:3584
	global_load_dwordx4 v[52:55], v[68:69], off
	global_load_dwordx4 v[56:59], v[70:71], off
	v_pk_add_f32 v[50:51], v[64:65], v[62:63]
	s_waitcnt vmcnt(0) lgkmcnt(0)
	v_pk_add_f32 v[58:59], v[58:59], 1.0 op_sel_hi:[1,0]
	v_pk_add_f32 v[50:51], v[50:51], v[66:67]
	v_pk_add_f32 v[56:57], v[56:57], 1.0 op_sel_hi:[1,0]
	v_add_f32_e32 v50, v50, v51
	ds_bpermute_b32 v51, v1, v50
	s_waitcnt lgkmcnt(0)
	v_add_f32_e32 v50, v50, v51
	ds_bpermute_b32 v51, v97, v50
	s_waitcnt lgkmcnt(0)
	v_add_f32_e32 v50, v50, v51
	ds_bpermute_b32 v51, v98, v50
	s_waitcnt lgkmcnt(0)
	v_add_f32_e32 v50, v50, v51
	ds_bpermute_b32 v51, v99, v50
	s_waitcnt lgkmcnt(0)
	v_add_f32_e32 v50, v50, v51
	ds_bpermute_b32 v51, v100, v50
	s_waitcnt lgkmcnt(0)
	v_add_f32_e32 v50, v50, v51
	ds_bpermute_b32 v51, v101, v50
	s_waitcnt lgkmcnt(0)
	v_add_f32_e32 v50, v50, v51
	v_fmamk_f32 v50, v50, 0x3a800000, v102
	v_mul_f32_e32 v51, 0x4f800000, v50
	v_cmp_gt_f32_e32 vcc, s4, v50
	s_nop 1
	v_cndmask_b32_e32 v60, v50, v51, vcc
	v_sqrt_f32_e32 v61, v60
	v_add_co_u32_e64 v50, s[6:7], s26, v86
	v_add_u32_e32 v62, -1, v61
	s_nop 0
	v_addc_co_u32_e64 v51, s[6:7], 0, v87, s[6:7]
	v_add_u32_e32 v63, 1, v61
	v_fma_f32 v64, -v62, v61, v60
	v_fma_f32 v65, -v63, v61, v60
	v_cmp_ge_f32_e64 s[6:7], 0, v64
	v_lshl_add_u64 v[86:87], v[86:87], 0, s[18:19]
	s_nop 0
	v_cndmask_b32_e64 v61, v61, v62, s[6:7]
	v_cmp_lt_f32_e64 s[6:7], 0, v65
	s_nop 1
	v_cndmask_b32_e64 v61, v61, v63, s[6:7]
	v_mul_f32_e32 v62, 0x37800000, v61
	v_cndmask_b32_e32 v61, v61, v62, vcc
	v_cmp_class_f32_e32 vcc, v60, v103
	s_and_b64 s[6:7], exec, s[24:25]
	s_nop 0
	v_cndmask_b32_e32 v62, v61, v60, vcc
	v_div_scale_f32 v63, s[6:7], v62, v62, 1.0
	v_rcp_f32_e32 v64, v63
	v_div_scale_f32 v65, vcc, 1.0, v62, 1.0
	v_lshl_add_u64 v[60:61], s[46:47], 0, v[90:91]
	v_fma_f32 v66, -v63, v64, 1.0
	v_fmac_f32_e32 v64, v66, v64
	v_mul_f32_e32 v66, v65, v64
	v_fma_f32 v67, -v63, v66, v65
	v_fmac_f32_e32 v66, v67, v64
	v_fma_f32 v63, -v63, v66, v65
	v_div_fmas_f32 v63, v63, v64, v66
	v_div_fixup_f32 v62, v63, v62, 1.0
	v_pk_mul_f32 v[48:49], v[48:49], v[62:63] op_sel_hi:[1,0]
	v_pk_mul_f32 v[46:47], v[46:47], v[62:63] op_sel_hi:[1,0]
	v_pk_mul_f32 v[48:49], v[4:5], v[48:49]
	v_pk_mul_f32 v[46:47], v[2:3], v[46:47]
	v_pk_fma_f32 v[48:49], v[58:59], v[48:49], v[54:55]
	v_pk_fma_f32 v[46:47], v[56:57], v[46:47], v[52:53]
	v_bfe_u32 v54, v48, 16, 1
	v_bfe_u32 v52, v46, 16, 1
	v_bfe_u32 v53, v47, 16, 1
	v_bfe_u32 v55, v49, 16, 1
	v_add3_u32 v46, v46, v52, s5
	v_add3_u32 v48, v48, v54, s5
	v_add3_u32 v47, v47, v53, s5
	v_add3_u32 v49, v49, v55, s5
	v_lshrrev_b32_e32 v46, 16, v46
	v_lshrrev_b32_e32 v48, 16, v48
	v_and_or_b32 v46, v47, s13, v46
	v_and_or_b32 v47, v49, s13, v48
	global_store_dwordx2 v[50:51], v[46:47], off
	global_load_dwordx4 v[46:49], v[60:61], off
	s_nop 0
	global_load_dwordx4 v[52:55], v[68:69], off offset:1024
	v_pk_mul_f32 v[40:41], v[40:41], v[62:63] op_sel_hi:[1,0]
	v_pk_mul_f32 v[38:39], v[38:39], v[62:63] op_sel_hi:[1,0]
	v_pk_mul_f32 v[40:41], v[8:9], v[40:41]
	v_pk_mul_f32 v[38:39], v[6:7], v[38:39]
	v_lshl_add_u64 v[56:57], s[46:47], 0, v[92:93]
	v_pk_mul_f32 v[32:33], v[32:33], v[62:63] op_sel_hi:[1,0]
	v_pk_mul_f32 v[30:31], v[30:31], v[62:63] op_sel_hi:[1,0]
	v_pk_mul_f32 v[32:33], v[12:13], v[32:33]
	v_pk_mul_f32 v[30:31], v[10:11], v[30:31]
	v_pk_mul_f32 v[20:21], v[20:21], v[62:63] op_sel_hi:[1,0]
	v_pk_mul_f32 v[18:19], v[18:19], v[62:63] op_sel_hi:[1,0]
	v_pk_mul_f32 v[20:21], v[16:17], v[20:21]
	v_pk_mul_f32 v[18:19], v[14:15], v[18:19]
	s_cselect_b32 s6, s27, s14
	s_mul_hi_i32 s7, s6, 0x9000
	s_mul_i32 s6, s6, 0x9000
	s_add_u32 s6, s42, s6
	s_addc_u32 s7, s43, s7
	s_lshl_b64 s[28:29], s[44:45], 11
	s_add_u32 s24, s6, 0x1000
	s_addc_u32 s25, s7, 0
	v_pk_mul_f32 v[58:59], v[34:35], v[34:35]
	v_mul_f32_e32 v63, v22, v22
	v_mul_f32_e32 v60, v27, v27
	v_mul_f32_e32 v62, v29, v29
	v_mul_f32_e32 v66, v23, v23
	v_mul_f32_e32 v67, v24, v24
	s_add_u32 s10, s10, s16
	s_addc_u32 s11, s11, s17
	s_add_u32 s20, s20, s22
	s_addc_u32 s21, s21, s23
	s_cmpk_lt_i32 s10, 0x4080
	s_waitcnt vmcnt(0) lgkmcnt(0)
	v_pk_add_f32 v[48:49], v[48:49], 1.0 op_sel_hi:[1,0]
	v_pk_add_f32 v[46:47], v[46:47], 1.0 op_sel_hi:[1,0]
	v_pk_fma_f32 v[40:41], v[48:49], v[40:41], v[54:55]
	v_pk_fma_f32 v[38:39], v[46:47], v[38:39], v[52:53]
	v_bfe_u32 v48, v40, 16, 1
	v_bfe_u32 v46, v38, 16, 1
	v_bfe_u32 v47, v39, 16, 1
	v_bfe_u32 v49, v41, 16, 1
	v_add3_u32 v38, v38, v46, s5
	v_add3_u32 v40, v40, v48, s5
	v_add3_u32 v39, v39, v47, s5
	v_add3_u32 v41, v41, v49, s5
	v_lshrrev_b32_e32 v38, 16, v38
	v_lshrrev_b32_e32 v40, 16, v40
	v_and_or_b32 v38, v39, s13, v38
	v_and_or_b32 v39, v41, s13, v40
	global_store_dwordx2 v[50:51], v[38:39], off offset:512
	global_load_dwordx4 v[38:41], v[56:57], off
	s_nop 0
	global_load_dwordx4 v[46:49], v[68:69], off offset:2048
	v_lshl_add_u64 v[52:53], s[46:47], 0, v[94:95]
	v_pk_mul_f32 v[54:55], v[42:43], v[42:43]
	v_pk_mul_f32 v[56:57], v[36:37], v[36:37]
	s_waitcnt vmcnt(0) lgkmcnt(0)
	v_pk_add_f32 v[40:41], v[40:41], 1.0 op_sel_hi:[1,0]
	v_pk_add_f32 v[38:39], v[38:39], 1.0 op_sel_hi:[1,0]
	v_pk_fma_f32 v[32:33], v[40:41], v[32:33], v[48:49]
	v_pk_fma_f32 v[30:31], v[38:39], v[30:31], v[46:47]
	v_bfe_u32 v40, v32, 16, 1
	v_bfe_u32 v38, v30, 16, 1
	v_bfe_u32 v39, v31, 16, 1
	v_bfe_u32 v41, v33, 16, 1
	v_add3_u32 v30, v30, v38, s5
	v_add3_u32 v32, v32, v40, s5
	v_add3_u32 v31, v31, v39, s5
	v_add3_u32 v33, v33, v41, s5
	v_lshrrev_b32_e32 v30, 16, v30
	v_lshrrev_b32_e32 v32, 16, v32
	v_and_or_b32 v30, v31, s13, v30
	v_and_or_b32 v31, v33, s13, v32
	global_store_dwordx2 v[50:51], v[30:31], off offset:1024
	global_load_dwordx4 v[38:41], v[52:53], off
	global_load_dwordx4 v[46:49], v[68:69], off offset:3072
	v_lshl_add_u64 v[30:31], s[6:7], 0, v[88:89]
	v_lshl_add_u64 v[32:33], s[24:25], 0, v[88:89]
	v_pk_mul_f32 v[52:53], v[44:45], v[44:45]
	v_mul_f32_e32 v68, v25, v25
	v_pk_mov_b32 v[64:65], v[54:55], v[52:53] op_sel:[1,0]
	v_mov_b32_e32 v55, v53
	v_pk_mov_b32 v[52:53], v[58:59], v[56:57] op_sel:[1,0]
	v_mov_b32_e32 v59, v57
	v_pk_add_f32 v[54:55], v[64:65], v[54:55]
	v_pk_add_f32 v[52:53], v[52:53], v[58:59]
	v_pk_fma_f32 v[56:57], v[26:27], v[26:27], v[60:61] op_sel_hi:[1,1,0]
	v_pk_fma_f32 v[60:61], v[28:29], v[28:29], v[62:63] op_sel_hi:[1,1,0]
	v_pk_add_f32 v[54:55], v[54:55], v[54:55] op_sel:[0,1] op_sel_hi:[1,0]
	v_pk_add_f32 v[52:53], v[52:53], v[52:53] op_sel:[0,1] op_sel_hi:[1,0]
	v_mov_b32_e32 v57, v67
	v_mov_b32_e32 v61, v68
	v_mov_b32_e32 v55, v63
	v_mov_b32_e32 v53, v66
	v_pk_add_f32 v[56:57], v[56:57], v[60:61]
	s_waitcnt vmcnt(0) lgkmcnt(0)
	v_pk_add_f32 v[40:41], v[40:41], 1.0 op_sel_hi:[1,0]
	v_pk_add_f32 v[38:39], v[38:39], 1.0 op_sel_hi:[1,0]
	v_pk_fma_f32 v[20:21], v[20:21], v[40:41], v[48:49]
	v_pk_fma_f32 v[18:19], v[18:19], v[38:39], v[46:47]
	v_bfe_u32 v40, v20, 16, 1
	v_bfe_u32 v38, v18, 16, 1
	v_bfe_u32 v39, v19, 16, 1
	v_bfe_u32 v41, v21, 16, 1
	v_add3_u32 v18, v18, v38, s5
	v_add3_u32 v20, v20, v40, s5
	v_add3_u32 v19, v19, v39, s5
	v_add3_u32 v21, v21, v41, s5
	v_lshrrev_b32_e32 v18, 16, v18
	v_lshrrev_b32_e32 v20, 16, v20
	v_and_or_b32 v18, v19, s13, v18
	v_and_or_b32 v19, v21, s13, v20
	global_store_dwordx2 v[50:51], v[18:19], off offset:1536
	global_load_dwordx4 v[18:21], v[30:31], off
	s_nop 0
	global_load_dwordx4 v[38:41], v[32:33], off
	v_pk_add_f32 v[32:33], v[54:55], v[52:53]
	v_lshl_add_u64 v[46:47], v[84:85], 0, s[28:29]
	v_pk_add_f32 v[32:33], v[32:33], v[56:57]
	s_waitcnt vmcnt(0) lgkmcnt(0)
	v_pk_add_f32 v[40:41], v[40:41], 1.0 op_sel_hi:[1,0]
	v_add_f32_e32 v32, v32, v33
	ds_bpermute_b32 v33, v1, v32
	v_pk_add_f32 v[38:39], v[38:39], 1.0 op_sel_hi:[1,0]
	s_waitcnt lgkmcnt(0)
	v_add_f32_e32 v32, v32, v33
	ds_bpermute_b32 v33, v97, v32
	s_waitcnt lgkmcnt(0)
	v_add_f32_e32 v32, v32, v33
	ds_bpermute_b32 v33, v98, v32
	s_waitcnt lgkmcnt(0)
	v_add_f32_e32 v32, v32, v33
	ds_bpermute_b32 v33, v99, v32
	s_waitcnt lgkmcnt(0)
	v_add_f32_e32 v32, v32, v33
	ds_bpermute_b32 v33, v100, v32
	s_waitcnt lgkmcnt(0)
	v_add_f32_e32 v32, v32, v33
	ds_bpermute_b32 v33, v101, v32
	s_waitcnt lgkmcnt(0)
	v_add_f32_e32 v32, v32, v33
	v_fmamk_f32 v32, v32, 0x3a800000, v102
	v_mul_f32_e32 v33, 0x4f800000, v32
	v_cmp_gt_f32_e32 vcc, s4, v32
	s_nop 1
	v_cndmask_b32_e32 v32, v32, v33, vcc
	v_sqrt_f32_e32 v33, v32
	s_nop 0
	v_add_u32_e32 v48, -1, v33
	v_add_u32_e32 v49, 1, v33
	v_fma_f32 v50, -v48, v33, v32
	v_fma_f32 v51, -v49, v33, v32
	v_cmp_ge_f32_e64 s[6:7], 0, v50
	s_nop 1
	v_cndmask_b32_e64 v33, v33, v48, s[6:7]
	v_cmp_lt_f32_e64 s[6:7], 0, v51
	s_nop 1
	v_cndmask_b32_e64 v33, v33, v49, s[6:7]
	v_mul_f32_e32 v48, 0x37800000, v33
	v_cndmask_b32_e32 v33, v33, v48, vcc
	v_cmp_class_f32_e32 vcc, v32, v103
	s_nop 1
	v_cndmask_b32_e32 v48, v33, v32, vcc
	v_div_scale_f32 v49, s[6:7], v48, v48, 1.0
	v_rcp_f32_e32 v50, v49
	v_div_scale_f32 v51, vcc, 1.0, v48, 1.0
	v_lshl_add_u64 v[32:33], s[24:25], 0, v[90:91]
	v_fma_f32 v52, -v49, v50, 1.0
	v_fmac_f32_e32 v50, v52, v50
	v_mul_f32_e32 v52, v51, v50
	v_fma_f32 v53, -v49, v52, v51
	v_fmac_f32_e32 v52, v53, v50
	v_fma_f32 v49, -v49, v52, v51
	v_div_fmas_f32 v49, v49, v50, v52
	v_div_fixup_f32 v48, v49, v48, 1.0
	v_pk_mul_f32 v[44:45], v[44:45], v[48:49] op_sel_hi:[1,0]
	v_pk_mul_f32 v[42:43], v[42:43], v[48:49] op_sel_hi:[1,0]
	v_pk_mul_f32 v[44:45], v[4:5], v[44:45]
	v_pk_mul_f32 v[42:43], v[2:3], v[42:43]
	v_pk_fma_f32 v[20:21], v[40:41], v[44:45], v[20:21]
	v_pk_fma_f32 v[18:19], v[38:39], v[42:43], v[18:19]
	v_bfe_u32 v40, v20, 16, 1
	v_bfe_u32 v38, v18, 16, 1
	v_bfe_u32 v39, v19, 16, 1
	v_bfe_u32 v41, v21, 16, 1
	v_add3_u32 v18, v18, v38, s5
	v_add3_u32 v20, v20, v40, s5
	v_add3_u32 v19, v19, v39, s5
	v_add3_u32 v21, v21, v41, s5
	v_lshrrev_b32_e32 v18, 16, v18
	v_lshrrev_b32_e32 v20, 16, v20
	v_and_or_b32 v18, v19, s13, v18
	v_and_or_b32 v19, v21, s13, v20
	global_store_dwordx2 v[46:47], v[18:19], off
	global_load_dwordx4 v[18:21], v[32:33], off
	s_nop 0
	global_load_dwordx4 v[38:41], v[30:31], off offset:1024
	v_pk_mul_f32 v[32:33], v[36:37], v[48:49] op_sel_hi:[1,0]
	v_pk_mul_f32 v[34:35], v[34:35], v[48:49] op_sel_hi:[1,0]
	v_pk_mul_f32 v[32:33], v[8:9], v[32:33]
	v_pk_mul_f32 v[34:35], v[6:7], v[34:35]
	v_lshl_add_u64 v[42:43], s[24:25], 0, v[92:93]
	v_pk_mul_f32 v[28:29], v[28:29], v[48:49] op_sel_hi:[1,0]
	v_pk_mul_f32 v[26:27], v[26:27], v[48:49] op_sel_hi:[1,0]
	v_pk_mul_f32 v[28:29], v[12:13], v[28:29]
	v_pk_mul_f32 v[26:27], v[10:11], v[26:27]
	v_lshl_add_u64 v[36:37], s[24:25], 0, v[94:95]
	v_pk_mul_f32 v[24:25], v[24:25], v[48:49] op_sel_hi:[1,0]
	v_pk_mul_f32 v[22:23], v[22:23], v[48:49] op_sel_hi:[1,0]
	v_pk_mul_f32 v[24:25], v[16:17], v[24:25]
	v_pk_mul_f32 v[22:23], v[14:15], v[22:23]
	s_waitcnt vmcnt(0) lgkmcnt(0)
	v_pk_add_f32 v[20:21], v[20:21], 1.0 op_sel_hi:[1,0]
	v_pk_add_f32 v[18:19], v[18:19], 1.0 op_sel_hi:[1,0]
	v_pk_fma_f32 v[20:21], v[20:21], v[32:33], v[40:41]
	v_pk_fma_f32 v[18:19], v[18:19], v[34:35], v[38:39]
	v_bfe_u32 v34, v20, 16, 1
	v_bfe_u32 v32, v18, 16, 1
	v_bfe_u32 v33, v19, 16, 1
	v_bfe_u32 v35, v21, 16, 1
	v_add3_u32 v18, v18, v32, s5
	v_add3_u32 v20, v20, v34, s5
	v_add3_u32 v19, v19, v33, s5
	v_add3_u32 v21, v21, v35, s5
	v_lshrrev_b32_e32 v18, 16, v18
	v_lshrrev_b32_e32 v20, 16, v20
	v_and_or_b32 v18, v19, s13, v18
	v_and_or_b32 v19, v21, s13, v20
	global_store_dwordx2 v[46:47], v[18:19], off offset:512
	global_load_dwordx4 v[18:21], v[42:43], off
	s_nop 0
	global_load_dwordx4 v[32:35], v[30:31], off offset:2048
	s_waitcnt vmcnt(0) lgkmcnt(0)
	v_pk_add_f32 v[20:21], v[20:21], 1.0 op_sel_hi:[1,0]
	v_pk_add_f32 v[18:19], v[18:19], 1.0 op_sel_hi:[1,0]
	v_pk_fma_f32 v[20:21], v[20:21], v[28:29], v[34:35]
	v_pk_fma_f32 v[18:19], v[18:19], v[26:27], v[32:33]
	v_bfe_u32 v28, v20, 16, 1
	v_bfe_u32 v26, v18, 16, 1
	v_bfe_u32 v27, v19, 16, 1
	v_bfe_u32 v29, v21, 16, 1
	v_add3_u32 v18, v18, v26, s5
	v_add3_u32 v20, v20, v28, s5
	v_add3_u32 v19, v19, v27, s5
	v_add3_u32 v21, v21, v29, s5
	v_lshrrev_b32_e32 v18, 16, v18
	v_lshrrev_b32_e32 v20, 16, v20
	v_and_or_b32 v18, v19, s13, v18
	v_and_or_b32 v19, v21, s13, v20
	global_store_dwordx2 v[46:47], v[18:19], off offset:1024
	global_load_dwordx4 v[18:21], v[36:37], off
	s_nop 0
	global_load_dwordx4 v[26:29], v[30:31], off offset:3072
	s_waitcnt vmcnt(0) lgkmcnt(0)
	v_pk_add_f32 v[20:21], v[20:21], 1.0 op_sel_hi:[1,0]
	v_pk_add_f32 v[18:19], v[18:19], 1.0 op_sel_hi:[1,0]
	v_pk_fma_f32 v[20:21], v[24:25], v[20:21], v[28:29]
	v_pk_fma_f32 v[18:19], v[22:23], v[18:19], v[26:27]
	v_bfe_u32 v24, v20, 16, 1
	v_bfe_u32 v22, v18, 16, 1
	v_bfe_u32 v23, v19, 16, 1
	v_bfe_u32 v25, v21, 16, 1
	v_add3_u32 v18, v18, v22, s5
	v_add3_u32 v20, v20, v24, s5
	v_add3_u32 v19, v19, v23, s5
	v_add3_u32 v21, v21, v25, s5
	v_lshrrev_b32_e32 v18, 16, v18
	v_lshrrev_b32_e32 v20, 16, v20
	v_and_or_b32 v18, v19, s13, v18
	v_and_or_b32 v19, v21, s13, v20
	global_store_dwordx2 v[46:47], v[18:19], off offset:1536
	s_cbranch_scc0 .LBB0_735
.LBB0_731:
	s_add_i32 s14, s10, 0xffffc000
	s_cmpk_lt_i32 s10, 0x4000
	s_cselect_b64 s[6:7], -1, 0
	s_and_b64 s[24:25], s[6:7], exec
	s_cselect_b32 s24, s1, s9
	s_cselect_b32 s25, s0, s8
	v_mov_b32_e32 v18, s25
	v_mov_b32_e32 v19, s24
	global_load_dwordx2 v[18:19], v[18:19], off sc0 sc1
	s_waitcnt vmcnt(0)
	s_cselect_b32 s25, s11, 0
	s_cselect_b32 s24, s10, s14
	s_lshl_b64 s[24:25], s[24:25], 12
	s_add_u32 s14, s10, 1
	s_addc_u32 s27, s11, 0
	s_add_i32 s30, s10, 0xffffc001
	s_cmpk_lt_i32 s14, 0x4000
	s_cselect_b64 s[48:49], -1, 0
	s_and_b64 s[28:29], s[48:49], exec
	s_cselect_b32 s28, s1, s9
	s_cselect_b32 s29, s0, s8
	v_mov_b32_e32 v20, s29
	v_mov_b32_e32 v21, s28
	s_mov_b64 s[52:53], -1
	s_waitcnt lgkmcnt(0)
	v_lshl_add_u64 v[18:19], v[18:19], 0, s[24:25]
	v_lshl_add_u64 v[18:19], v[18:19], 0, v[82:83]
	global_load_dwordx4 v[78:81], v[18:19], off
	global_load_dwordx4 v[74:77], v[18:19], off offset:1024
	global_load_dwordx4 v[70:73], v[18:19], off offset:2048
	global_load_dwordx4 v[66:69], v[18:19], off offset:3072
	s_nop 0
	global_load_dwordx2 v[18:19], v[20:21], off sc0 sc1
	s_waitcnt vmcnt(0)
	s_cselect_b32 s25, s27, 0
	s_cselect_b32 s24, s14, s30
	s_lshl_b64 s[24:25], s[24:25], 12
	s_add_u32 s14, s10, 2
	s_addc_u32 s27, s11, 0
	s_add_i32 s28, s10, 0xffffc002
	s_cmpk_lt_i32 s14, 0x4000
	s_cselect_b64 s[46:47], -1, 0
	s_and_b64 s[30:31], s[46:47], exec
	s_cselect_b32 s29, s1, s9
	s_cselect_b32 s30, s0, s8
	v_mov_b32_e32 v20, s30
	v_mov_b32_e32 v21, s29
	s_waitcnt lgkmcnt(0)
	v_lshl_add_u64 v[18:19], v[18:19], 0, s[24:25]
	v_lshl_add_u64 v[18:19], v[18:19], 0, v[82:83]
	global_load_dwordx4 v[62:65], v[18:19], off
	global_load_dwordx4 v[58:61], v[18:19], off offset:1024
	global_load_dwordx4 v[54:57], v[18:19], off offset:2048
	global_load_dwordx4 v[50:53], v[18:19], off offset:3072
	s_nop 0
	global_load_dwordx2 v[18:19], v[20:21], off sc0 sc1
	s_waitcnt vmcnt(0)
	s_cselect_b32 s25, s27, 0
	s_cselect_b32 s24, s14, s28
	s_lshl_b64 s[24:25], s[24:25], 12
	s_add_u32 s50, s10, 3
	s_addc_u32 s51, s11, 0
	s_cmpk_lt_i32 s50, 0x4000
	s_waitcnt lgkmcnt(0)
	v_lshl_add_u64 v[18:19], v[18:19], 0, s[24:25]
	v_lshl_add_u64 v[18:19], v[18:19], 0, v[82:83]
	global_load_dwordx4 v[46:49], v[18:19], off
	global_load_dwordx4 v[38:41], v[18:19], off offset:1024
	global_load_dwordx4 v[30:33], v[18:19], off offset:2048
	s_nop 0
	global_load_dwordx4 v[18:21], v[18:19], off offset:3072
	s_cselect_b64 s[24:25], -1, 0
	s_and_b64 vcc, exec, s[24:25]
	s_cbranch_vccnz .LBB0_733
	v_mov_b64_e32 v[22:23], s[8:9]
	global_load_dwordx2 v[22:23], v[22:23], off sc0 sc1
	s_waitcnt vmcnt(0)
	s_add_i32 s14, s10, 0xffffc003
	s_lshl_b64 s[30:31], s[14:15], 12
	s_mov_b32 s44, s50
	s_mov_b32 s45, s15
	s_mov_b64 s[52:53], 0
	s_waitcnt lgkmcnt(0)
	v_lshl_add_u64 v[22:23], v[22:23], 0, s[30:31]
.LBB0_733:
	s_andn2_b64 vcc, exec, s[52:53]
	s_cbranch_vccnz .LBB0_730
	v_mov_b64_e32 v[22:23], s[0:1]
	global_load_dwordx2 v[22:23], v[22:23], off sc0 sc1
	s_waitcnt vmcnt(0)
	s_add_i32 s14, s10, 0xffffc003
	s_mov_b64 s[44:45], s[50:51]
	s_waitcnt lgkmcnt(0)
	v_lshl_add_u64 v[22:23], v[22:23], 0, s[20:21]
	s_branch .LBB0_730

.LBB0_789:
	s_waitcnt lgkmcnt(0)
	v_mov_b64_e32 v[2:3], s[0:1]
	global_load_dwordx2 v[134:135], v[2:3], off sc0 sc1
	s_waitcnt vmcnt(0)
	global_load_dwordx2 v[136:137], v[2:3], off offset:8 sc0 sc1
	s_waitcnt vmcnt(0)
	s_cmp_lt_i32 s90, 3
	s_cselect_b64 s[4:5], -1, 0
	s_cmp_gt_i32 s91, 2
	s_cselect_b64 s[6:7], -1, 0
	s_and_b64 s[14:15], s[4:5], s[6:7]
	s_andn2_b64 vcc, exec, s[14:15]
	s_cbranch_vccnz .LBB0_882
	s_add_u32 s4, s38, 0x200000
	s_addc_u32 s5, s39, 0
	s_add_u32 s6, s38, 0x8000
	s_addc_u32 s7, s39, 0
	s_add_u32 s16, s38, 0x10000000
	s_addc_u32 s17, s39, 0
	s_cmp_gt_i32 s40, 21
	s_cbranch_scc1 .LBB0_801
	v_mov_b32_e32 v10, v0
	s_mov_b32 s8, 0x1fffe0
	v_ashrrev_i32_e32 v2, 31, v10
	v_lshrrev_b32_e32 v2, 26, v2
	v_add_u32_e32 v2, v10, v2
	v_ashrrev_i32_e32 v6, 6, v2
	v_bfe_i32 v2, v10, 27, 1
	v_lshlrev_b32_e32 v1, 4, v10
	v_lshrrev_b32_e32 v2, 22, v2
	v_add_u32_e32 v2, v1, v2
	v_and_b32_e32 v2, 0xfffffc00, v2
	v_sub_u32_e32 v2, v1, v2
	v_lshrrev_b32_e32 v3, 4, v2
	v_bitop3_b32 v2, v3, v2, 32 bitop3:0x6c
	v_ashrrev_i32_e32 v4, 31, v2
	v_lshrrev_b32_e32 v4, 26, v4
	v_add_u32_e32 v4, v2, v4
	v_lshlrev_b32_e32 v3, 3, v6
	v_ashrrev_i32_e32 v7, 6, v4
	v_and_b32_e32 v4, 0xc0, v4
	v_and_b32_e32 v3, -16, v3
	v_sub_u32_e32 v2, v2, v4
	v_mov_b32_e32 v4, 1
	v_add_u32_e32 v3, v7, v3
	v_ashrrev_i16_sdwa v2, v4, sext(v2) dst_sel:DWORD dst_unused:UNUSED_PAD src0_sel:DWORD src1_sel:BYTE_0
	v_lshlrev_b32_e32 v5, 5, v6
	v_bfe_i32 v8, v2, 0, 16
	v_lshlrev_b32_e32 v2, 1, v3
	v_lshrrev_b32_e32 v9, 2, v3
	v_and_b32_e32 v11, 3, v7
	v_and_b32_e32 v5, 32, v5
	v_and_b32_e32 v2, 24, v2
	v_and_b32_e32 v9, 4, v9
	v_and_or_b32 v11, v3, s8, v11
	v_or3_b32 v2, v11, v9, v2
	v_add_lshl_u32 v5, v5, v8, 1
	v_add_u32_e32 v1, 0x2000, v1
	v_lshl_add_u32 v140, v2, 11, v5
	v_ashrrev_i32_e32 v2, 31, v1
	v_lshrrev_b32_e32 v2, 22, v2
	v_add_u32_e32 v2, v1, v2
	v_ashrrev_i32_e32 v9, 10, v2
	v_mul_i32_i24_e32 v2, 0x400, v9
	v_sub_u32_e32 v1, v1, v2
	v_lshrrev_b32_e32 v2, 4, v1
	v_bitop3_b32 v1, v2, v1, 32 bitop3:0x6c
	v_lshl_add_u32 v138, v3, 11, v5
	v_ashrrev_i32_e32 v3, 31, v1
	v_lshrrev_b32_e32 v3, 26, v3
	v_add_u32_e32 v3, v1, v3
	v_readfirstlane_b32 s13, v10
	v_lshlrev_b32_e32 v2, 3, v9
	v_ashrrev_i32_e32 v11, 6, v3
	v_and_b32_e32 v3, 0xc0, v3
	v_and_b32_e32 v2, -16, v2
	v_sub_u32_e32 v1, v1, v3
	s_ashr_i32 s19, s13, 6
	s_ashr_i32 s41, s40, 31
	s_ashr_i32 s18, s13, 8
	v_add_u32_e32 v2, v11, v2
	v_ashrrev_i16_sdwa v1, v4, sext(v1) dst_sel:DWORD dst_unused:UNUSED_PAD src0_sel:DWORD src1_sel:BYTE_0
	v_and_b32_e32 v4, 3, v11
	s_lshl_b32 s24, s19, 10
	s_lshl_b64 s[20:21], s[40:41], 19
	v_and_or_b32 v4, v2, s8, v4
	s_add_u32 s8, s4, s20
	s_addc_u32 s9, s5, s21
	s_add_i32 s22, s96, 0x10000
	s_add_i32 s26, s22, s24
	v_lshlrev_b32_e32 v5, 5, v9
	v_bfe_i32 v12, v1, 0, 16
	v_lshlrev_b32_e32 v1, 1, v2
	v_lshrrev_b32_e32 v3, 2, v2
	s_add_i32 s27, s26, 0x2000
	v_and_b32_e32 v5, 32, v5
	v_and_b32_e32 v1, 24, v1
	v_and_b32_e32 v3, 4, v3
	s_add_u32 s10, s8, 0x40000
	v_or3_b32 v1, v4, v3, v1
	v_add_lshl_u32 v3, v5, v12, 1
	s_mov_b32 m0, s26
	s_addc_u32 s11, s9, 0
	s_add_i32 s23, s96, 0x14000
	v_lshl_add_u32 v144, v1, 11, v3
	global_load_lds_dwordx4 v140, s[8:9]
	s_mov_b32 m0, s27
	s_add_i32 s28, s23, s24
	global_load_lds_dwordx4 v144, s[8:9]
	s_mov_b32 m0, s28
	s_add_i32 s29, s28, 0x2000
	global_load_lds_dwordx4 v140, s[10:11]
	s_mov_b32 m0, s29
	v_lshl_add_u32 v142, v2, 11, v3
	global_load_lds_dwordx4 v144, s[10:11]
	s_add_u32 s10, s38, 0xda00000
	s_addc_u32 s11, s39, 0
	s_add_i32 s30, s96, s24
	s_add_i32 s31, s30, 0x2000
	s_mov_b32 m0, s30
	s_add_u32 s44, s38, 0xda40000
	global_load_lds_dwordx4 v138, s[10:11]
	s_mov_b32 m0, s31
	s_addc_u32 s45, s39, 0
	s_add_i32 s33, s30, 0x4000
	global_load_lds_dwordx4 v142, s[10:11]
	s_mov_b32 m0, s33
	s_add_i32 s34, s30, 0x6000
	global_load_lds_dwordx4 v138, s[44:45]
	s_mov_b32 m0, s34
	v_mov_b32_e32 v141, 0
	global_load_lds_dwordx4 v142, s[44:45]
	v_mov_b32_e32 v145, v141
	v_lshl_add_u64 v[4:5], s[8:9], 0, v[140:141]
	v_lshl_add_u64 v[2:3], s[8:9], 0, v[144:145]
	v_mov_b32_e32 v139, v141
	s_cmp_lg_u32 s18, 1
	v_mov_b32_e32 v143, v141
	s_cbranch_scc1 .LBB0_793
	s_barrier

.LBB0_797:
	v_mul_f32_e32 v133, 0xbfb8aa3b, v126
	v_exp_f32_e32 v133, v133
	s_lshl_b32 s10, s40, 7
	v_mul_f32_e32 v144, 0xbfb8aa3b, v127
	v_exp_f32_e32 v144, v144
	v_add_f32_e32 v133, 1.0, v133
	v_div_scale_f32 v141, s[8:9], v133, v133, v126
	v_rcp_f32_e32 v142, v141
	s_or_b32 s8, s35, s10
	v_or_b32_e32 v138, s8, v131
	v_add_u32_e32 v140, 0x4000, v1
	v_fma_f32 v131, -v141, v142, 1.0
	v_fmac_f32_e32 v142, v131, v142
	v_div_scale_f32 v131, vcc, v126, v133, v126
	v_mul_f32_e32 v143, v131, v142
	v_fma_f32 v145, -v141, v143, v131
	v_fmac_f32_e32 v143, v145, v142
	v_fma_f32 v131, -v141, v143, v131
	v_add_f32_e32 v141, 1.0, v144
	v_div_scale_f32 v144, s[8:9], v141, v141, v127
	v_rcp_f32_e32 v145, v144
	v_div_fmas_f32 v131, v131, v142, v143
	v_div_fixup_f32 v126, v131, v133, v126
	v_mul_f32_e32 v122, v126, v122
	v_fma_f32 v126, -v144, v145, 1.0
	v_fmac_f32_e32 v145, v126, v145
	v_div_scale_f32 v126, vcc, v127, v141, v127
	v_mul_f32_e32 v131, v126, v145
	v_fma_f32 v133, -v144, v131, v126
	v_fmac_f32_e32 v131, v133, v145
	v_mul_f32_e32 v133, 0xbfb8aa3b, v128
	v_exp_f32_e32 v133, v133
	v_fma_f32 v126, -v144, v131, v126
	v_div_fmas_f32 v126, v126, v145, v131
	v_div_fixup_f32 v126, v126, v141, v127
	v_add_f32_e32 v131, 1.0, v133
	v_div_scale_f32 v133, s[8:9], v131, v131, v128
	v_rcp_f32_e32 v142, v133
	v_mul_f32_e32 v123, v126, v123
	v_mul_f32_e32 v127, 0xbfb8aa3b, v129
	v_cvt_pk_bf16_f32 v122, v122, v123
	v_fma_f32 v123, -v133, v142, 1.0
	v_exp_f32_e32 v127, v127
	v_fmac_f32_e32 v142, v123, v142
	v_div_scale_f32 v123, vcc, v128, v131, v128
	v_mul_f32_e32 v126, v123, v142
	v_fma_f32 v141, -v133, v126, v123
	v_fmac_f32_e32 v126, v141, v142
	v_add_f32_e32 v127, 1.0, v127
	v_fma_f32 v123, -v133, v126, v123
	v_div_scale_f32 v133, s[8:9], v127, v127, v129
	v_rcp_f32_e32 v141, v133
	v_div_fmas_f32 v123, v123, v142, v126
	v_div_fixup_f32 v123, v123, v131, v128
	v_mul_f32_e32 v123, v123, v124
	v_fma_f32 v124, -v133, v141, 1.0
	v_fmac_f32_e32 v141, v124, v141
	v_div_scale_f32 v124, vcc, v129, v127, v129
	v_mul_f32_e32 v126, v124, v141
	v_fma_f32 v128, -v133, v126, v124
	v_fmac_f32_e32 v126, v128, v141
	v_mul_f32_e32 v128, 0xbfb8aa3b, v118
	v_exp_f32_e32 v128, v128
	v_fma_f32 v124, -v133, v126, v124
	v_div_fmas_f32 v124, v124, v141, v126
	v_div_fixup_f32 v124, v124, v127, v129
	v_add_f32_e32 v126, 1.0, v128
	v_div_scale_f32 v128, s[8:9], v126, v126, v118
	v_rcp_f32_e32 v131, v128
	v_mul_f32_e32 v124, v124, v125
	v_mul_f32_e32 v127, 0xbfb8aa3b, v119
	v_cvt_pk_bf16_f32 v123, v123, v124
	v_fma_f32 v124, -v128, v131, 1.0
	v_exp_f32_e32 v127, v127
	v_fmac_f32_e32 v131, v124, v131
	v_div_scale_f32 v124, vcc, v118, v126, v118
	v_mul_f32_e32 v125, v124, v131
	v_fma_f32 v129, -v128, v125, v124
	v_fmac_f32_e32 v125, v129, v131
	v_add_f32_e32 v127, 1.0, v127
	v_fma_f32 v124, -v128, v125, v124
	v_div_scale_f32 v128, s[8:9], v127, v127, v119
	v_rcp_f32_e32 v129, v128
	v_div_fmas_f32 v124, v124, v131, v125
	v_div_fixup_f32 v118, v124, v126, v118
	v_mul_f32_e32 v114, v118, v114
	v_fma_f32 v118, -v128, v129, 1.0
	v_fmac_f32_e32 v129, v118, v129
	v_div_scale_f32 v118, vcc, v119, v127, v119
	v_mul_f32_e32 v124, v118, v129
	v_fma_f32 v125, -v128, v124, v118
	v_fmac_f32_e32 v124, v125, v129
	v_mul_f32_e32 v125, 0xbfb8aa3b, v120
	v_exp_f32_e32 v125, v125
	v_fma_f32 v118, -v128, v124, v118
	v_div_fmas_f32 v118, v118, v129, v124
	v_div_fixup_f32 v118, v118, v127, v119
	v_add_f32_e32 v125, 1.0, v125
	v_div_scale_f32 v126, s[8:9], v125, v125, v120
	v_rcp_f32_e32 v128, v126
	v_mul_f32_e32 v115, v118, v115
	v_mul_f32_e32 v118, 0xbfb8aa3b, v121
	v_exp_f32_e32 v118, v118
	v_cvt_pk_bf16_f32 v124, v114, v115
	v_fma_f32 v114, -v126, v128, 1.0
	v_fmac_f32_e32 v128, v114, v128
	v_div_scale_f32 v114, vcc, v120, v125, v120
	v_mul_f32_e32 v115, v114, v128
	v_fma_f32 v119, -v126, v115, v114
	v_add_f32_e32 v118, 1.0, v118
	v_fmac_f32_e32 v115, v119, v128
	v_div_scale_f32 v119, s[8:9], v118, v118, v121
	v_fma_f32 v114, -v126, v115, v114
	v_rcp_f32_e32 v126, v119
	v_div_fmas_f32 v114, v114, v128, v115
	v_div_fixup_f32 v114, v114, v125, v120
	v_mul_f32_e32 v114, v114, v116
	v_fma_f32 v115, -v119, v126, 1.0
	v_fmac_f32_e32 v126, v115, v126
	v_div_scale_f32 v115, vcc, v121, v118, v121
	v_mul_f32_e32 v116, v115, v126
	v_fma_f32 v120, -v119, v116, v115
	v_fmac_f32_e32 v116, v120, v126
	v_fma_f32 v115, -v119, v116, v115
	v_div_fmas_f32 v115, v115, v126, v116
	v_div_fixup_f32 v115, v115, v118, v121
	v_mul_f32_e32 v115, v115, v117
	v_cvt_pk_bf16_f32 v125, v114, v115
	v_mul_f32_e32 v114, 0xbfb8aa3b, v110
	v_exp_f32_e32 v116, v114
	v_ashrrev_i32_e32 v139, 31, v138
	s_movk_i32 s8, 0x1600
	v_mov_b64_e32 v[114:115], s[16:17]
	v_add_f32_e32 v120, 1.0, v116
	v_div_scale_f32 v121, s[10:11], v120, v120, v110
	v_rcp_f32_e32 v126, v121
	v_mad_i64_i32 v[118:119], s[10:11], v140, s8, v[114:115]
	v_lshlrev_b64 v[116:117], 1, v[138:139]
	v_lshl_add_u64 v[118:119], v[118:119], 0, v[116:117]
	global_store_dwordx4 v[118:119], v[122:125], off
	v_fma_f32 v118, -v121, v126, 1.0
	v_fmac_f32_e32 v126, v118, v126
	v_mul_f32_e32 v122, 0xbfb8aa3b, v111
	v_div_scale_f32 v118, vcc, v110, v120, v110
	v_exp_f32_e32 v122, v122
	v_mul_f32_e32 v119, v118, v126
	v_fma_f32 v123, -v121, v119, v118
	v_fmac_f32_e32 v119, v123, v126
	v_fma_f32 v118, -v121, v119, v118
	v_add_f32_e32 v121, 1.0, v122
	v_div_scale_f32 v122, s[10:11], v121, v121, v111
	v_rcp_f32_e32 v123, v122
	v_div_fmas_f32 v118, v118, v126, v119
	v_div_fixup_f32 v110, v118, v120, v110
	v_mul_f32_e32 v106, v110, v106
	v_fma_f32 v110, -v122, v123, 1.0
	v_fmac_f32_e32 v123, v110, v123
	v_div_scale_f32 v110, vcc, v111, v121, v111
	v_mul_f32_e32 v118, v110, v123
	v_fma_f32 v119, -v122, v118, v110
	v_fmac_f32_e32 v118, v119, v123
	v_mul_f32_e32 v119, 0xbfb8aa3b, v112
	v_exp_f32_e32 v119, v119
	v_fma_f32 v110, -v122, v118, v110
	v_div_fmas_f32 v110, v110, v123, v118
	v_div_fixup_f32 v110, v110, v121, v111
	v_add_f32_e32 v118, 1.0, v119
	v_div_scale_f32 v119, s[10:11], v118, v118, v112
	v_rcp_f32_e32 v120, v119
	v_mul_f32_e32 v107, v110, v107
	v_mul_f32_e32 v111, 0xbfb8aa3b, v113
	v_cvt_pk_bf16_f32 v106, v106, v107
	v_fma_f32 v107, -v119, v120, 1.0
	v_exp_f32_e32 v111, v111
	v_fmac_f32_e32 v120, v107, v120
	v_div_scale_f32 v107, vcc, v112, v118, v112
	v_mul_f32_e32 v110, v107, v120
	v_fma_f32 v121, -v119, v110, v107
	v_fmac_f32_e32 v110, v121, v120
	v_add_f32_e32 v111, 1.0, v111
	v_fma_f32 v107, -v119, v110, v107
	v_div_scale_f32 v119, s[10:11], v111, v111, v113
	v_rcp_f32_e32 v121, v119
	v_div_fmas_f32 v107, v107, v120, v110
	v_div_fixup_f32 v107, v107, v118, v112
	v_mul_f32_e32 v107, v107, v108
	v_fma_f32 v108, -v119, v121, 1.0
	v_fmac_f32_e32 v121, v108, v121
	v_div_scale_f32 v108, vcc, v113, v111, v113
	v_mul_f32_e32 v110, v108, v121
	v_fma_f32 v112, -v119, v110, v108
	v_fmac_f32_e32 v110, v112, v121
	v_mul_f32_e32 v112, 0xbfb8aa3b, v102
	v_exp_f32_e32 v112, v112
	v_fma_f32 v108, -v119, v110, v108
	v_div_fmas_f32 v108, v108, v121, v110
	v_div_fixup_f32 v108, v108, v111, v113
	v_add_f32_e32 v110, 1.0, v112
	v_div_scale_f32 v112, s[10:11], v110, v110, v102
	v_rcp_f32_e32 v118, v112
	v_mul_f32_e32 v108, v108, v109
	v_mul_f32_e32 v111, 0xbfb8aa3b, v103
	v_cvt_pk_bf16_f32 v107, v107, v108
	v_fma_f32 v108, -v112, v118, 1.0
	v_exp_f32_e32 v111, v111
	v_fmac_f32_e32 v118, v108, v118
	v_div_scale_f32 v108, vcc, v102, v110, v102
	v_mul_f32_e32 v109, v108, v118
	v_fma_f32 v113, -v112, v109, v108
	v_fmac_f32_e32 v109, v113, v118
	v_add_f32_e32 v111, 1.0, v111
	v_fma_f32 v108, -v112, v109, v108
	v_div_scale_f32 v112, s[10:11], v111, v111, v103
	v_rcp_f32_e32 v113, v112
	v_div_fmas_f32 v108, v108, v118, v109
	v_div_fixup_f32 v102, v108, v110, v102
	v_mul_f32_e32 v98, v102, v98
	v_fma_f32 v102, -v112, v113, 1.0
	v_fmac_f32_e32 v113, v102, v113
	v_div_scale_f32 v102, vcc, v103, v111, v103
	v_mul_f32_e32 v108, v102, v113
	v_fma_f32 v109, -v112, v108, v102
	v_fmac_f32_e32 v108, v109, v113
	v_mul_f32_e32 v109, 0xbfb8aa3b, v104
	v_exp_f32_e32 v109, v109
	v_fma_f32 v102, -v112, v108, v102
	v_div_fmas_f32 v102, v102, v113, v108
	v_div_fixup_f32 v102, v102, v111, v103
	v_add_f32_e32 v109, 1.0, v109
	v_div_scale_f32 v110, s[10:11], v109, v109, v104
	v_rcp_f32_e32 v112, v110
	v_mul_f32_e32 v99, v102, v99
	v_mul_f32_e32 v102, 0xbfb8aa3b, v105
	v_exp_f32_e32 v102, v102
	v_cvt_pk_bf16_f32 v108, v98, v99
	v_fma_f32 v98, -v110, v112, 1.0
	v_fmac_f32_e32 v112, v98, v112
	v_div_scale_f32 v98, vcc, v104, v109, v104
	v_mul_f32_e32 v99, v98, v112
	v_fma_f32 v103, -v110, v99, v98
	v_add_f32_e32 v102, 1.0, v102
	v_fmac_f32_e32 v99, v103, v112
	v_div_scale_f32 v103, s[10:11], v102, v102, v105
	v_fma_f32 v98, -v110, v99, v98
	v_rcp_f32_e32 v110, v103
	v_div_fmas_f32 v98, v98, v112, v99
	v_div_fixup_f32 v98, v98, v109, v104
	v_mul_f32_e32 v98, v98, v100
	v_fma_f32 v99, -v103, v110, 1.0
	v_fmac_f32_e32 v110, v99, v110
	v_div_scale_f32 v99, vcc, v105, v102, v105
	v_mul_f32_e32 v100, v99, v110
	v_fma_f32 v104, -v103, v100, v99
	v_fmac_f32_e32 v100, v104, v110
	v_fma_f32 v99, -v103, v100, v99
	v_div_fmas_f32 v99, v99, v110, v100
	v_mul_f32_e32 v100, 0xbfb8aa3b, v94
	v_exp_f32_e32 v100, v100
	v_div_fixup_f32 v99, v99, v102, v105
	v_mul_f32_e32 v99, v99, v101
	v_cvt_pk_bf16_f32 v109, v98, v99
	v_add_f32_e32 v100, 1.0, v100
	v_div_scale_f32 v101, s[10:11], v100, v100, v94
	v_rcp_f32_e32 v102, v101
	v_add_u32_e32 v98, 0x4010, v1
	v_mad_i64_i32 v[98:99], s[10:11], v98, s8, v[114:115]
	v_lshl_add_u64 v[98:99], v[98:99], 0, v[116:117]
	global_store_dwordx4 v[98:99], v[106:109], off
	v_fma_f32 v98, -v101, v102, 1.0
	v_mul_f32_e32 v103, 0xbfb8aa3b, v95
	v_fmac_f32_e32 v102, v98, v102
	v_div_scale_f32 v98, vcc, v94, v100, v94
	v_exp_f32_e32 v103, v103
	v_mul_f32_e32 v99, v98, v102
	v_fma_f32 v104, -v101, v99, v98
	v_fmac_f32_e32 v99, v104, v102
	v_fma_f32 v98, -v101, v99, v98
	v_add_f32_e32 v101, 1.0, v103
	v_div_scale_f32 v103, s[10:11], v101, v101, v95
	v_rcp_f32_e32 v104, v103
	v_div_fmas_f32 v98, v98, v102, v99
	v_div_fixup_f32 v94, v98, v100, v94
	v_mul_f32_e32 v90, v94, v90
	v_fma_f32 v94, -v103, v104, 1.0
	v_fmac_f32_e32 v104, v94, v104
	v_div_scale_f32 v94, vcc, v95, v101, v95
	v_mul_f32_e32 v98, v94, v104
	v_fma_f32 v99, -v103, v98, v94
	v_fmac_f32_e32 v98, v99, v104
	v_mul_f32_e32 v99, 0xbfb8aa3b, v96
	v_exp_f32_e32 v99, v99
	v_fma_f32 v94, -v103, v98, v94
	v_div_fmas_f32 v94, v94, v104, v98
	v_div_fixup_f32 v94, v94, v101, v95
	v_add_f32_e32 v98, 1.0, v99
	v_div_scale_f32 v99, s[10:11], v98, v98, v96
	v_rcp_f32_e32 v100, v99
	v_mul_f32_e32 v91, v94, v91
	v_mul_f32_e32 v95, 0xbfb8aa3b, v97
	v_cvt_pk_bf16_f32 v90, v90, v91
	v_fma_f32 v91, -v99, v100, 1.0
	v_exp_f32_e32 v95, v95
	v_fmac_f32_e32 v100, v91, v100
	v_div_scale_f32 v91, vcc, v96, v98, v96
	v_mul_f32_e32 v94, v91, v100
	v_fma_f32 v101, -v99, v94, v91
	v_fmac_f32_e32 v94, v101, v100
	v_add_f32_e32 v95, 1.0, v95
	v_fma_f32 v91, -v99, v94, v91
	v_div_scale_f32 v99, s[10:11], v95, v95, v97
	v_rcp_f32_e32 v101, v99
	v_div_fmas_f32 v91, v91, v100, v94
	v_div_fixup_f32 v91, v91, v98, v96
	v_mul_f32_e32 v91, v91, v92
	v_fma_f32 v92, -v99, v101, 1.0
	v_fmac_f32_e32 v101, v92, v101
	v_div_scale_f32 v92, vcc, v97, v95, v97
	v_mul_f32_e32 v94, v92, v101
	v_fma_f32 v96, -v99, v94, v92
	v_fmac_f32_e32 v94, v96, v101
	v_mul_f32_e32 v96, 0xbfb8aa3b, v86
	v_exp_f32_e32 v96, v96
	v_fma_f32 v92, -v99, v94, v92
	v_div_fmas_f32 v92, v92, v101, v94
	v_div_fixup_f32 v92, v92, v95, v97
	v_add_f32_e32 v94, 1.0, v96
	v_div_scale_f32 v96, s[10:11], v94, v94, v86
	v_rcp_f32_e32 v98, v96
	v_mul_f32_e32 v92, v92, v93
	v_mul_f32_e32 v95, 0xbfb8aa3b, v87
	v_cvt_pk_bf16_f32 v91, v91, v92
	v_fma_f32 v92, -v96, v98, 1.0
	v_exp_f32_e32 v95, v95
	v_fmac_f32_e32 v98, v92, v98
	v_div_scale_f32 v92, vcc, v86, v94, v86
	v_mul_f32_e32 v93, v92, v98
	v_fma_f32 v97, -v96, v93, v92
	v_fmac_f32_e32 v93, v97, v98
	v_add_f32_e32 v95, 1.0, v95
	v_fma_f32 v92, -v96, v93, v92
	v_div_scale_f32 v96, s[10:11], v95, v95, v87
	v_rcp_f32_e32 v97, v96
	v_div_fmas_f32 v92, v92, v98, v93
	v_div_fixup_f32 v86, v92, v94, v86
	v_mul_f32_e32 v82, v86, v82
	v_fma_f32 v86, -v96, v97, 1.0
	v_fmac_f32_e32 v97, v86, v97
	v_div_scale_f32 v86, vcc, v87, v95, v87
	v_mul_f32_e32 v92, v86, v97
	v_fma_f32 v93, -v96, v92, v86
	v_fmac_f32_e32 v92, v93, v97
	v_mul_f32_e32 v93, 0xbfb8aa3b, v88
	v_exp_f32_e32 v93, v93
	v_fma_f32 v86, -v96, v92, v86
	v_div_fmas_f32 v86, v86, v97, v92
	v_div_fixup_f32 v86, v86, v95, v87
	v_add_f32_e32 v93, 1.0, v93
	v_div_scale_f32 v94, s[10:11], v93, v93, v88
	v_rcp_f32_e32 v96, v94
	v_mul_f32_e32 v83, v86, v83
	v_mul_f32_e32 v86, 0xbfb8aa3b, v89
	v_exp_f32_e32 v86, v86
	v_cvt_pk_bf16_f32 v92, v82, v83
	v_fma_f32 v82, -v94, v96, 1.0
	v_fmac_f32_e32 v96, v82, v96
	v_div_scale_f32 v82, vcc, v88, v93, v88
	v_mul_f32_e32 v83, v82, v96
	v_fma_f32 v87, -v94, v83, v82
	v_add_f32_e32 v86, 1.0, v86
	v_fmac_f32_e32 v83, v87, v96
	v_div_scale_f32 v87, s[10:11], v86, v86, v89
	v_fma_f32 v82, -v94, v83, v82
	v_rcp_f32_e32 v94, v87
	v_div_fmas_f32 v82, v82, v96, v83
	v_div_fixup_f32 v82, v82, v93, v88
	v_mul_f32_e32 v82, v82, v84
	v_fma_f32 v83, -v87, v94, 1.0
	v_fmac_f32_e32 v94, v83, v94
	v_div_scale_f32 v83, vcc, v89, v86, v89
	v_mul_f32_e32 v84, v83, v94
	v_fma_f32 v88, -v87, v84, v83
	v_fmac_f32_e32 v84, v88, v94
	v_fma_f32 v83, -v87, v84, v83
	v_div_fmas_f32 v83, v83, v94, v84
	v_mul_f32_e32 v84, 0xbfb8aa3b, v78
	v_exp_f32_e32 v84, v84
	v_div_fixup_f32 v83, v83, v86, v89
	v_mul_f32_e32 v83, v83, v85
	v_cvt_pk_bf16_f32 v93, v82, v83
	v_add_f32_e32 v84, 1.0, v84
	v_div_scale_f32 v85, s[10:11], v84, v84, v78
	v_rcp_f32_e32 v86, v85
	v_add_u32_e32 v82, 0x4020, v1
	v_mad_i64_i32 v[82:83], s[10:11], v82, s8, v[114:115]
	v_lshl_add_u64 v[82:83], v[82:83], 0, v[116:117]
	global_store_dwordx4 v[82:83], v[90:93], off
	v_fma_f32 v82, -v85, v86, 1.0
	v_mul_f32_e32 v87, 0xbfb8aa3b, v79
	v_fmac_f32_e32 v86, v82, v86
	v_div_scale_f32 v82, vcc, v78, v84, v78
	v_exp_f32_e32 v87, v87
	v_mul_f32_e32 v83, v82, v86
	v_fma_f32 v88, -v85, v83, v82
	v_fmac_f32_e32 v83, v88, v86
	v_fma_f32 v82, -v85, v83, v82
	v_add_f32_e32 v85, 1.0, v87
	v_div_scale_f32 v87, s[10:11], v85, v85, v79
	v_rcp_f32_e32 v88, v87
	v_div_fmas_f32 v82, v82, v86, v83
	v_div_fixup_f32 v78, v82, v84, v78
	v_mul_f32_e32 v74, v78, v74
	v_fma_f32 v78, -v87, v88, 1.0
	v_fmac_f32_e32 v88, v78, v88
	v_div_scale_f32 v78, vcc, v79, v85, v79
	v_mul_f32_e32 v82, v78, v88
	v_fma_f32 v83, -v87, v82, v78
	v_fmac_f32_e32 v82, v83, v88
	v_mul_f32_e32 v83, 0xbfb8aa3b, v80
	v_exp_f32_e32 v83, v83
	v_fma_f32 v78, -v87, v82, v78
	v_div_fmas_f32 v78, v78, v88, v82
	v_div_fixup_f32 v78, v78, v85, v79
	v_add_f32_e32 v82, 1.0, v83
	v_div_scale_f32 v83, s[10:11], v82, v82, v80
	v_rcp_f32_e32 v84, v83
	v_mul_f32_e32 v75, v78, v75
	v_mul_f32_e32 v79, 0xbfb8aa3b, v81
	v_cvt_pk_bf16_f32 v74, v74, v75
	v_fma_f32 v75, -v83, v84, 1.0
	v_exp_f32_e32 v79, v79
	v_fmac_f32_e32 v84, v75, v84
	v_div_scale_f32 v75, vcc, v80, v82, v80
	v_mul_f32_e32 v78, v75, v84
	v_fma_f32 v85, -v83, v78, v75
	v_fmac_f32_e32 v78, v85, v84
	v_add_f32_e32 v79, 1.0, v79
	v_fma_f32 v75, -v83, v78, v75
	v_div_scale_f32 v83, s[10:11], v79, v79, v81
	v_rcp_f32_e32 v85, v83
	v_div_fmas_f32 v75, v75, v84, v78
	v_div_fixup_f32 v75, v75, v82, v80
	v_mul_f32_e32 v75, v75, v76
	v_fma_f32 v76, -v83, v85, 1.0
	v_fmac_f32_e32 v85, v76, v85
	v_div_scale_f32 v76, vcc, v81, v79, v81
	v_mul_f32_e32 v78, v76, v85
	v_fma_f32 v80, -v83, v78, v76
	v_fmac_f32_e32 v78, v80, v85
	v_mul_f32_e32 v80, 0xbfb8aa3b, v70
	v_exp_f32_e32 v80, v80
	v_fma_f32 v76, -v83, v78, v76
	v_div_fmas_f32 v76, v76, v85, v78
	v_div_fixup_f32 v76, v76, v79, v81
	v_add_f32_e32 v78, 1.0, v80
	v_div_scale_f32 v80, s[10:11], v78, v78, v70
	v_rcp_f32_e32 v82, v80
	v_mul_f32_e32 v76, v76, v77
	v_mul_f32_e32 v79, 0xbfb8aa3b, v71
	v_cvt_pk_bf16_f32 v75, v75, v76
	v_fma_f32 v76, -v80, v82, 1.0
	v_exp_f32_e32 v79, v79
	v_fmac_f32_e32 v82, v76, v82
	v_div_scale_f32 v76, vcc, v70, v78, v70
	v_mul_f32_e32 v77, v76, v82
	v_fma_f32 v81, -v80, v77, v76
	v_fmac_f32_e32 v77, v81, v82
	v_add_f32_e32 v79, 1.0, v79
	v_fma_f32 v76, -v80, v77, v76
	v_div_scale_f32 v80, s[10:11], v79, v79, v71
	v_rcp_f32_e32 v81, v80
	v_div_fmas_f32 v76, v76, v82, v77
	v_div_fixup_f32 v70, v76, v78, v70
	v_mul_f32_e32 v66, v70, v66
	v_fma_f32 v70, -v80, v81, 1.0
	v_fmac_f32_e32 v81, v70, v81
	v_div_scale_f32 v70, vcc, v71, v79, v71
	v_mul_f32_e32 v76, v70, v81
	v_fma_f32 v77, -v80, v76, v70
	v_fmac_f32_e32 v76, v77, v81
	v_mul_f32_e32 v77, 0xbfb8aa3b, v72
	v_exp_f32_e32 v77, v77
	v_fma_f32 v70, -v80, v76, v70
	v_div_fmas_f32 v70, v70, v81, v76
	v_div_fixup_f32 v70, v70, v79, v71
	v_add_f32_e32 v77, 1.0, v77
	v_div_scale_f32 v78, s[10:11], v77, v77, v72
	v_rcp_f32_e32 v80, v78
	v_mul_f32_e32 v67, v70, v67
	v_mul_f32_e32 v70, 0xbfb8aa3b, v73
	v_exp_f32_e32 v70, v70
	v_cvt_pk_bf16_f32 v76, v66, v67
	v_fma_f32 v66, -v78, v80, 1.0
	v_fmac_f32_e32 v80, v66, v80
	v_div_scale_f32 v66, vcc, v72, v77, v72
	v_mul_f32_e32 v67, v66, v80
	v_fma_f32 v71, -v78, v67, v66
	v_add_f32_e32 v70, 1.0, v70
	v_fmac_f32_e32 v67, v71, v80
	v_div_scale_f32 v71, s[10:11], v70, v70, v73
	v_fma_f32 v66, -v78, v67, v66
	v_rcp_f32_e32 v78, v71
	v_div_fmas_f32 v66, v66, v80, v67
	v_div_fixup_f32 v66, v66, v77, v72
	v_mul_f32_e32 v66, v66, v68
	v_fma_f32 v67, -v71, v78, 1.0
	v_fmac_f32_e32 v78, v67, v78
	v_div_scale_f32 v67, vcc, v73, v70, v73
	v_mul_f32_e32 v68, v67, v78
	v_fma_f32 v72, -v71, v68, v67
	v_fmac_f32_e32 v68, v72, v78
	v_fma_f32 v67, -v71, v68, v67
	v_div_fmas_f32 v67, v67, v78, v68
	v_div_fixup_f32 v67, v67, v70, v73
	v_mul_f32_e32 v67, v67, v69
	v_cvt_pk_bf16_f32 v77, v66, v67
	v_mul_f32_e32 v66, 0xbfb8aa3b, v62
	v_exp_f32_e32 v68, v66
	v_add_u32_e32 v66, 0x4030, v1
	v_mad_i64_i32 v[66:67], s[10:11], v66, s8, v[114:115]
	v_add_f32_e32 v68, 1.0, v68
	v_div_scale_f32 v69, s[10:11], v68, v68, v62
	v_rcp_f32_e32 v70, v69
	v_lshl_add_u64 v[66:67], v[66:67], 0, v[116:117]
	global_store_dwordx4 v[66:67], v[74:77], off
	v_mul_f32_e32 v72, 0xbfb8aa3b, v63
	v_fma_f32 v67, -v69, v70, 1.0
	v_fmac_f32_e32 v70, v67, v70
	v_div_scale_f32 v67, vcc, v62, v68, v62
	v_exp_f32_e32 v72, v72
	v_mul_f32_e32 v71, v67, v70
	v_fma_f32 v73, -v69, v71, v67
	v_fmac_f32_e32 v71, v73, v70
	v_fma_f32 v67, -v69, v71, v67
	v_add_f32_e32 v69, 1.0, v72
	v_div_scale_f32 v72, s[10:11], v69, v69, v63
	v_rcp_f32_e32 v73, v72
	v_div_fmas_f32 v67, v67, v70, v71
	v_div_fixup_f32 v62, v67, v68, v62
	v_mul_f32_e32 v58, v62, v58
	v_fma_f32 v62, -v72, v73, 1.0
	v_fmac_f32_e32 v73, v62, v73
	v_div_scale_f32 v62, vcc, v63, v69, v63
	v_mul_f32_e32 v67, v62, v73
	v_fma_f32 v68, -v72, v67, v62
	v_fmac_f32_e32 v67, v68, v73
	v_mul_f32_e32 v68, 0xbfb8aa3b, v64
	v_exp_f32_e32 v68, v68
	v_fma_f32 v62, -v72, v67, v62
	v_div_fmas_f32 v62, v62, v73, v67
	v_div_fixup_f32 v62, v62, v69, v63
	v_add_f32_e32 v67, 1.0, v68
	v_div_scale_f32 v68, s[10:11], v67, v67, v64
	v_rcp_f32_e32 v70, v68
	v_mul_f32_e32 v59, v62, v59
	v_mul_f32_e32 v63, 0xbfb8aa3b, v65
	v_cvt_pk_bf16_f32 v58, v58, v59
	v_fma_f32 v59, -v68, v70, 1.0
	v_exp_f32_e32 v63, v63
	v_fmac_f32_e32 v70, v59, v70
	v_div_scale_f32 v59, vcc, v64, v67, v64
	v_mul_f32_e32 v62, v59, v70
	v_fma_f32 v69, -v68, v62, v59
	v_fmac_f32_e32 v62, v69, v70
	v_add_f32_e32 v63, 1.0, v63
	v_fma_f32 v59, -v68, v62, v59
	v_div_scale_f32 v68, s[10:11], v63, v63, v65
	v_rcp_f32_e32 v69, v68
	v_div_fmas_f32 v59, v59, v70, v62
	v_div_fixup_f32 v59, v59, v67, v64
	v_mul_f32_e32 v59, v59, v60
	v_fma_f32 v60, -v68, v69, 1.0
	v_fmac_f32_e32 v69, v60, v69
	v_div_scale_f32 v60, vcc, v65, v63, v65
	v_mul_f32_e32 v62, v60, v69
	v_fma_f32 v64, -v68, v62, v60
	v_fmac_f32_e32 v62, v64, v69
	v_mul_f32_e32 v64, 0xbfb8aa3b, v54
	v_exp_f32_e32 v64, v64
	v_fma_f32 v60, -v68, v62, v60
	v_div_fmas_f32 v60, v60, v69, v62
	v_div_fixup_f32 v60, v60, v63, v65
	v_add_f32_e32 v62, 1.0, v64
	v_div_scale_f32 v64, s[10:11], v62, v62, v54
	v_rcp_f32_e32 v67, v64
	v_mul_f32_e32 v60, v60, v61
	v_mul_f32_e32 v63, 0xbfb8aa3b, v55
	v_cvt_pk_bf16_f32 v59, v59, v60
	v_fma_f32 v60, -v64, v67, 1.0
	v_exp_f32_e32 v63, v63
	v_fmac_f32_e32 v67, v60, v67
	v_div_scale_f32 v60, vcc, v54, v62, v54
	v_mul_f32_e32 v61, v60, v67
	v_fma_f32 v65, -v64, v61, v60
	v_fmac_f32_e32 v61, v65, v67
	v_add_f32_e32 v63, 1.0, v63
	v_fma_f32 v60, -v64, v61, v60
	v_div_scale_f32 v64, s[10:11], v63, v63, v55
	v_rcp_f32_e32 v65, v64
	v_div_fmas_f32 v60, v60, v67, v61
	v_div_fixup_f32 v54, v60, v62, v54
	v_mul_f32_e32 v50, v54, v50
	v_fma_f32 v54, -v64, v65, 1.0
	v_fmac_f32_e32 v65, v54, v65
	v_div_scale_f32 v54, vcc, v55, v63, v55
	v_mul_f32_e32 v60, v54, v65
	v_fma_f32 v61, -v64, v60, v54
	v_fmac_f32_e32 v60, v61, v65
	v_mul_f32_e32 v61, 0xbfb8aa3b, v56
	v_exp_f32_e32 v61, v61
	v_fma_f32 v54, -v64, v60, v54
	v_div_fmas_f32 v54, v54, v65, v60
	v_div_fixup_f32 v54, v54, v63, v55
	v_add_f32_e32 v61, 1.0, v61
	v_div_scale_f32 v62, s[10:11], v61, v61, v56
	v_rcp_f32_e32 v64, v62
	v_mul_f32_e32 v51, v54, v51
	v_mul_f32_e32 v54, 0xbfb8aa3b, v57
	v_exp_f32_e32 v54, v54
	v_cvt_pk_bf16_f32 v60, v50, v51
	v_fma_f32 v50, -v62, v64, 1.0
	v_fmac_f32_e32 v64, v50, v64
	v_div_scale_f32 v50, vcc, v56, v61, v56
	v_mul_f32_e32 v51, v50, v64
	v_fma_f32 v55, -v62, v51, v50
	v_add_f32_e32 v54, 1.0, v54
	v_fmac_f32_e32 v51, v55, v64
	v_div_scale_f32 v55, s[10:11], v54, v54, v57
	v_fma_f32 v50, -v62, v51, v50
	v_rcp_f32_e32 v62, v55
	v_div_fmas_f32 v50, v50, v64, v51
	v_div_fixup_f32 v50, v50, v61, v56
	v_mul_f32_e32 v50, v50, v52
	v_fma_f32 v51, -v55, v62, 1.0
	v_fmac_f32_e32 v62, v51, v62
	v_div_scale_f32 v51, vcc, v57, v54, v57
	v_mul_f32_e32 v52, v51, v62
	v_fma_f32 v56, -v55, v52, v51
	v_fmac_f32_e32 v52, v56, v62
	v_fma_f32 v51, -v55, v52, v51
	v_div_fmas_f32 v51, v51, v62, v52
	v_mul_f32_e32 v52, 0xbfb8aa3b, v46
	v_exp_f32_e32 v52, v52
	v_div_fixup_f32 v51, v51, v54, v57
	v_mul_f32_e32 v51, v51, v53
	v_add_u32_e32 v66, 0x4080, v1
	v_add_f32_e32 v52, 1.0, v52
	v_div_scale_f32 v53, s[10:11], v52, v52, v46
	v_rcp_f32_e32 v54, v53
	v_cvt_pk_bf16_f32 v61, v50, v51
	v_mad_i64_i32 v[50:51], s[10:11], v66, s8, v[114:115]
	v_lshl_add_u64 v[50:51], v[50:51], 0, v[116:117]
	global_store_dwordx4 v[50:51], v[58:61], off
	v_fma_f32 v50, -v53, v54, 1.0
	v_mul_f32_e32 v55, 0xbfb8aa3b, v47
	v_fmac_f32_e32 v54, v50, v54
	v_div_scale_f32 v50, vcc, v46, v52, v46
	v_exp_f32_e32 v55, v55
	v_mul_f32_e32 v51, v50, v54
	v_fma_f32 v56, -v53, v51, v50
	v_fmac_f32_e32 v51, v56, v54
	v_fma_f32 v50, -v53, v51, v50
	v_add_f32_e32 v53, 1.0, v55
	v_div_scale_f32 v55, s[10:11], v53, v53, v47
	v_rcp_f32_e32 v56, v55
	v_div_fmas_f32 v50, v50, v54, v51
	v_div_fixup_f32 v46, v50, v52, v46
	v_mul_f32_e32 v42, v46, v42
	v_fma_f32 v46, -v55, v56, 1.0
	v_fmac_f32_e32 v56, v46, v56
	v_div_scale_f32 v46, vcc, v47, v53, v47
	v_mul_f32_e32 v50, v46, v56
	v_fma_f32 v51, -v55, v50, v46
	v_fmac_f32_e32 v50, v51, v56
	v_mul_f32_e32 v51, 0xbfb8aa3b, v48
	v_exp_f32_e32 v51, v51
	v_fma_f32 v46, -v55, v50, v46
	v_div_fmas_f32 v46, v46, v56, v50
	v_div_fixup_f32 v46, v46, v53, v47
	v_add_f32_e32 v50, 1.0, v51
	v_div_scale_f32 v51, s[10:11], v50, v50, v48
	v_rcp_f32_e32 v52, v51
	v_mul_f32_e32 v43, v46, v43
	v_mul_f32_e32 v47, 0xbfb8aa3b, v49
	v_cvt_pk_bf16_f32 v42, v42, v43
	v_fma_f32 v43, -v51, v52, 1.0
	v_exp_f32_e32 v47, v47
	v_fmac_f32_e32 v52, v43, v52
	v_div_scale_f32 v43, vcc, v48, v50, v48
	v_mul_f32_e32 v46, v43, v52
	v_fma_f32 v53, -v51, v46, v43
	v_fmac_f32_e32 v46, v53, v52
	v_add_f32_e32 v47, 1.0, v47
	v_fma_f32 v43, -v51, v46, v43
	v_div_scale_f32 v51, s[10:11], v47, v47, v49
	v_rcp_f32_e32 v53, v51
	v_div_fmas_f32 v43, v43, v52, v46
	v_div_fixup_f32 v43, v43, v50, v48
	v_mul_f32_e32 v43, v43, v44
	v_fma_f32 v44, -v51, v53, 1.0
	v_fmac_f32_e32 v53, v44, v53
	v_div_scale_f32 v44, vcc, v49, v47, v49
	v_mul_f32_e32 v46, v44, v53
	v_fma_f32 v48, -v51, v46, v44
	v_fmac_f32_e32 v46, v48, v53
	v_mul_f32_e32 v48, 0xbfb8aa3b, v38
	v_exp_f32_e32 v48, v48
	v_fma_f32 v44, -v51, v46, v44
	v_div_fmas_f32 v44, v44, v53, v46
	v_div_fixup_f32 v44, v44, v47, v49
	v_add_f32_e32 v46, 1.0, v48
	v_div_scale_f32 v48, s[10:11], v46, v46, v38
	v_rcp_f32_e32 v50, v48
	v_mul_f32_e32 v44, v44, v45
	v_mul_f32_e32 v47, 0xbfb8aa3b, v39
	v_cvt_pk_bf16_f32 v43, v43, v44
	v_fma_f32 v44, -v48, v50, 1.0
	v_exp_f32_e32 v47, v47
	v_fmac_f32_e32 v50, v44, v50
	v_div_scale_f32 v44, vcc, v38, v46, v38
	v_mul_f32_e32 v45, v44, v50
	v_fma_f32 v49, -v48, v45, v44
	v_fmac_f32_e32 v45, v49, v50
	v_add_f32_e32 v47, 1.0, v47
	v_fma_f32 v44, -v48, v45, v44
	v_div_scale_f32 v48, s[10:11], v47, v47, v39
	v_rcp_f32_e32 v49, v48
	v_div_fmas_f32 v44, v44, v50, v45
	v_div_fixup_f32 v38, v44, v46, v38
	v_mul_f32_e32 v34, v38, v34
	v_fma_f32 v38, -v48, v49, 1.0
	v_fmac_f32_e32 v49, v38, v49
	v_div_scale_f32 v38, vcc, v39, v47, v39
	v_mul_f32_e32 v44, v38, v49
	v_fma_f32 v45, -v48, v44, v38
	v_fmac_f32_e32 v44, v45, v49
	v_mul_f32_e32 v45, 0xbfb8aa3b, v40
	v_exp_f32_e32 v45, v45
	v_fma_f32 v38, -v48, v44, v38
	v_div_fmas_f32 v38, v38, v49, v44
	v_div_fixup_f32 v38, v38, v47, v39
	v_add_f32_e32 v45, 1.0, v45
	v_div_scale_f32 v46, s[10:11], v45, v45, v40
	v_rcp_f32_e32 v48, v46
	v_mul_f32_e32 v35, v38, v35
	v_mul_f32_e32 v38, 0xbfb8aa3b, v41
	v_exp_f32_e32 v38, v38
	v_cvt_pk_bf16_f32 v44, v34, v35
	v_fma_f32 v34, -v46, v48, 1.0
	v_fmac_f32_e32 v48, v34, v48
	v_div_scale_f32 v34, vcc, v40, v45, v40
	v_mul_f32_e32 v35, v34, v48
	v_fma_f32 v39, -v46, v35, v34
	v_add_f32_e32 v38, 1.0, v38
	v_fmac_f32_e32 v35, v39, v48
	v_div_scale_f32 v39, s[10:11], v38, v38, v41
	v_fma_f32 v34, -v46, v35, v34
	v_rcp_f32_e32 v46, v39
	v_div_fmas_f32 v34, v34, v48, v35
	v_div_fixup_f32 v34, v34, v45, v40
	v_mul_f32_e32 v34, v34, v36
	v_fma_f32 v35, -v39, v46, 1.0
	v_fmac_f32_e32 v46, v35, v46
	v_div_scale_f32 v35, vcc, v41, v38, v41
	v_mul_f32_e32 v36, v35, v46
	v_fma_f32 v40, -v39, v36, v35
	v_fmac_f32_e32 v36, v40, v46
	v_fma_f32 v35, -v39, v36, v35
	v_div_fmas_f32 v35, v35, v46, v36
	v_mul_f32_e32 v36, 0xbfb8aa3b, v30
	v_exp_f32_e32 v36, v36
	v_div_fixup_f32 v35, v35, v38, v41
	v_mul_f32_e32 v35, v35, v37
	v_cvt_pk_bf16_f32 v45, v34, v35
	v_add_f32_e32 v36, 1.0, v36
	v_div_scale_f32 v37, s[10:11], v36, v36, v30
	v_rcp_f32_e32 v38, v37
	v_add_u32_e32 v34, 0x4090, v1
	v_mad_i64_i32 v[34:35], s[10:11], v34, s8, v[114:115]
	v_lshl_add_u64 v[34:35], v[34:35], 0, v[116:117]
	global_store_dwordx4 v[34:35], v[42:45], off
	v_fma_f32 v34, -v37, v38, 1.0
	v_mul_f32_e32 v39, 0xbfb8aa3b, v31
	v_fmac_f32_e32 v38, v34, v38
	v_div_scale_f32 v34, vcc, v30, v36, v30
	v_exp_f32_e32 v39, v39
	v_mul_f32_e32 v35, v34, v38
	v_fma_f32 v40, -v37, v35, v34
	v_fmac_f32_e32 v35, v40, v38
	v_fma_f32 v34, -v37, v35, v34
	v_add_f32_e32 v37, 1.0, v39
	v_div_scale_f32 v39, s[10:11], v37, v37, v31
	v_rcp_f32_e32 v40, v39
	v_div_fmas_f32 v34, v34, v38, v35
	v_div_fixup_f32 v30, v34, v36, v30
	v_mul_f32_e32 v26, v30, v26
	v_fma_f32 v30, -v39, v40, 1.0
	v_fmac_f32_e32 v40, v30, v40
	v_div_scale_f32 v30, vcc, v31, v37, v31
	v_mul_f32_e32 v34, v30, v40
	v_fma_f32 v35, -v39, v34, v30
	v_fmac_f32_e32 v34, v35, v40
	v_mul_f32_e32 v35, 0xbfb8aa3b, v32
	v_exp_f32_e32 v35, v35
	v_fma_f32 v30, -v39, v34, v30
	v_div_fmas_f32 v30, v30, v40, v34
	v_div_fixup_f32 v30, v30, v37, v31
	v_add_f32_e32 v34, 1.0, v35
	v_div_scale_f32 v35, s[10:11], v34, v34, v32
	v_rcp_f32_e32 v36, v35
	v_mul_f32_e32 v27, v30, v27
	v_mul_f32_e32 v31, 0xbfb8aa3b, v33
	v_cvt_pk_bf16_f32 v26, v26, v27
	v_fma_f32 v27, -v35, v36, 1.0
	v_exp_f32_e32 v31, v31
	v_fmac_f32_e32 v36, v27, v36
	v_div_scale_f32 v27, vcc, v32, v34, v32
	v_mul_f32_e32 v30, v27, v36
	v_fma_f32 v37, -v35, v30, v27
	v_fmac_f32_e32 v30, v37, v36
	v_add_f32_e32 v31, 1.0, v31
	v_fma_f32 v27, -v35, v30, v27
	v_div_scale_f32 v35, s[10:11], v31, v31, v33
	v_rcp_f32_e32 v37, v35
	v_div_fmas_f32 v27, v27, v36, v30
	v_div_fixup_f32 v27, v27, v34, v32
	v_mul_f32_e32 v27, v27, v28
	v_fma_f32 v28, -v35, v37, 1.0
	v_fmac_f32_e32 v37, v28, v37
	v_div_scale_f32 v28, vcc, v33, v31, v33
	v_mul_f32_e32 v30, v28, v37
	v_fma_f32 v32, -v35, v30, v28
	v_fmac_f32_e32 v30, v32, v37
	v_mul_f32_e32 v32, 0xbfb8aa3b, v22
	v_exp_f32_e32 v32, v32
	v_fma_f32 v28, -v35, v30, v28
	v_div_fmas_f32 v28, v28, v37, v30
	v_div_fixup_f32 v28, v28, v31, v33
	v_add_f32_e32 v30, 1.0, v32
	v_div_scale_f32 v32, s[10:11], v30, v30, v22
	v_rcp_f32_e32 v34, v32
	v_mul_f32_e32 v28, v28, v29
	v_mul_f32_e32 v31, 0xbfb8aa3b, v23
	v_cvt_pk_bf16_f32 v27, v27, v28
	v_fma_f32 v28, -v32, v34, 1.0
	v_exp_f32_e32 v31, v31
	v_fmac_f32_e32 v34, v28, v34
	v_div_scale_f32 v28, vcc, v22, v30, v22
	v_mul_f32_e32 v29, v28, v34
	v_fma_f32 v33, -v32, v29, v28
	v_fmac_f32_e32 v29, v33, v34
	v_add_f32_e32 v31, 1.0, v31
	v_fma_f32 v28, -v32, v29, v28
	v_div_scale_f32 v32, s[10:11], v31, v31, v23
	v_rcp_f32_e32 v33, v32
	v_div_fmas_f32 v28, v28, v34, v29
	v_div_fixup_f32 v22, v28, v30, v22
	v_mul_f32_e32 v18, v22, v18
	v_fma_f32 v22, -v32, v33, 1.0
	v_fmac_f32_e32 v33, v22, v33
	v_div_scale_f32 v22, vcc, v23, v31, v23
	v_mul_f32_e32 v28, v22, v33
	v_fma_f32 v29, -v32, v28, v22
	v_fmac_f32_e32 v28, v29, v33
	v_mul_f32_e32 v29, 0xbfb8aa3b, v24
	v_exp_f32_e32 v29, v29
	v_fma_f32 v22, -v32, v28, v22
	v_div_fmas_f32 v22, v22, v33, v28
	v_div_fixup_f32 v22, v22, v31, v23
	v_add_f32_e32 v29, 1.0, v29
	v_div_scale_f32 v30, s[10:11], v29, v29, v24
	v_rcp_f32_e32 v32, v30
	v_mul_f32_e32 v19, v22, v19
	v_mul_f32_e32 v22, 0xbfb8aa3b, v25
	v_exp_f32_e32 v22, v22
	v_cvt_pk_bf16_f32 v28, v18, v19
	v_fma_f32 v18, -v30, v32, 1.0
	v_fmac_f32_e32 v32, v18, v32
	v_div_scale_f32 v18, vcc, v24, v29, v24
	v_mul_f32_e32 v19, v18, v32
	v_fma_f32 v23, -v30, v19, v18
	v_add_f32_e32 v22, 1.0, v22
	v_fmac_f32_e32 v19, v23, v32
	v_div_scale_f32 v23, s[10:11], v22, v22, v25
	v_fma_f32 v18, -v30, v19, v18
	v_rcp_f32_e32 v30, v23
	v_div_fmas_f32 v18, v18, v32, v19
	v_div_fixup_f32 v18, v18, v29, v24
	v_mul_f32_e32 v18, v18, v20
	v_fma_f32 v19, -v23, v30, 1.0
	v_fmac_f32_e32 v30, v19, v30
	v_div_scale_f32 v19, vcc, v25, v22, v25
	v_mul_f32_e32 v20, v19, v30
	v_fma_f32 v24, -v23, v20, v19
	v_fmac_f32_e32 v20, v24, v30
	v_fma_f32 v19, -v23, v20, v19
	v_div_fmas_f32 v19, v19, v30, v20
	v_mul_f32_e32 v20, 0xbfb8aa3b, v14
	v_exp_f32_e32 v20, v20
	v_div_fixup_f32 v19, v19, v22, v25
	v_mul_f32_e32 v19, v19, v21
	v_cvt_pk_bf16_f32 v29, v18, v19
	v_add_f32_e32 v20, 1.0, v20
	v_div_scale_f32 v21, s[10:11], v20, v20, v14
	v_rcp_f32_e32 v22, v21
	v_add_u32_e32 v18, 0x40a0, v1
	v_mad_i64_i32 v[18:19], s[10:11], v18, s8, v[114:115]
	v_lshl_add_u64 v[18:19], v[18:19], 0, v[116:117]
	global_store_dwordx4 v[18:19], v[26:29], off
	v_fma_f32 v18, -v21, v22, 1.0
	v_mul_f32_e32 v23, 0xbfb8aa3b, v15
	v_fmac_f32_e32 v22, v18, v22
	v_div_scale_f32 v18, vcc, v14, v20, v14
	v_exp_f32_e32 v23, v23
	v_mul_f32_e32 v19, v18, v22
	v_fma_f32 v24, -v21, v19, v18
	v_fmac_f32_e32 v19, v24, v22
	v_fma_f32 v18, -v21, v19, v18
	v_add_f32_e32 v21, 1.0, v23
	v_div_scale_f32 v23, s[10:11], v21, v21, v15
	v_rcp_f32_e32 v24, v23
	v_div_fmas_f32 v18, v18, v22, v19
	v_div_fixup_f32 v14, v18, v20, v14
	v_mul_f32_e32 v10, v14, v10
	v_fma_f32 v14, -v23, v24, 1.0
	v_fmac_f32_e32 v24, v14, v24
	v_div_scale_f32 v14, vcc, v15, v21, v15
	v_mul_f32_e32 v18, v14, v24
	v_fma_f32 v19, -v23, v18, v14
	v_fmac_f32_e32 v18, v19, v24
	v_mul_f32_e32 v19, 0xbfb8aa3b, v16
	v_exp_f32_e32 v19, v19
	v_fma_f32 v14, -v23, v18, v14
	v_div_fmas_f32 v14, v14, v24, v18
	v_div_fixup_f32 v14, v14, v21, v15
	v_add_f32_e32 v18, 1.0, v19
	v_div_scale_f32 v19, s[10:11], v18, v18, v16
	v_rcp_f32_e32 v20, v19
	v_mul_f32_e32 v11, v14, v11
	v_mul_f32_e32 v15, 0xbfb8aa3b, v17
	v_cvt_pk_bf16_f32 v10, v10, v11
	v_fma_f32 v11, -v19, v20, 1.0
	v_exp_f32_e32 v15, v15
	v_fmac_f32_e32 v20, v11, v20
	v_div_scale_f32 v11, vcc, v16, v18, v16
	v_mul_f32_e32 v14, v11, v20
	v_fma_f32 v21, -v19, v14, v11
	v_fmac_f32_e32 v14, v21, v20
	v_add_f32_e32 v15, 1.0, v15
	v_fma_f32 v11, -v19, v14, v11
	v_div_scale_f32 v19, s[10:11], v15, v15, v17
	v_rcp_f32_e32 v21, v19
	v_div_fmas_f32 v11, v11, v20, v14
	v_div_fixup_f32 v11, v11, v18, v16
	v_mul_f32_e32 v11, v11, v12
	v_fma_f32 v12, -v19, v21, 1.0
	v_fmac_f32_e32 v21, v12, v21
	v_div_scale_f32 v12, vcc, v17, v15, v17
	v_mul_f32_e32 v14, v12, v21
	v_fma_f32 v16, -v19, v14, v12
	v_fmac_f32_e32 v14, v16, v21
	v_mul_f32_e32 v16, 0xbfb8aa3b, v6
	v_exp_f32_e32 v16, v16
	v_fma_f32 v12, -v19, v14, v12
	v_div_fmas_f32 v12, v12, v21, v14
	v_div_fixup_f32 v12, v12, v15, v17
	v_add_f32_e32 v14, 1.0, v16
	v_div_scale_f32 v16, s[10:11], v14, v14, v6
	v_rcp_f32_e32 v18, v16
	v_mul_f32_e32 v12, v12, v13
	v_mul_f32_e32 v15, 0xbfb8aa3b, v7
	v_cvt_pk_bf16_f32 v11, v11, v12
	v_fma_f32 v12, -v16, v18, 1.0
	v_exp_f32_e32 v15, v15
	v_fmac_f32_e32 v18, v12, v18
	v_div_scale_f32 v12, vcc, v6, v14, v6
	v_mul_f32_e32 v13, v12, v18
	v_fma_f32 v17, -v16, v13, v12
	v_fmac_f32_e32 v13, v17, v18
	v_add_f32_e32 v15, 1.0, v15
	v_fma_f32 v12, -v16, v13, v12
	v_div_scale_f32 v16, s[10:11], v15, v15, v7
	v_rcp_f32_e32 v17, v16
	v_div_fmas_f32 v12, v12, v18, v13
	v_div_fixup_f32 v6, v12, v14, v6
	v_mul_f32_e32 v2, v6, v2
	v_fma_f32 v6, -v16, v17, 1.0
	v_fmac_f32_e32 v17, v6, v17
	v_div_scale_f32 v6, vcc, v7, v15, v7
	v_mul_f32_e32 v12, v6, v17
	v_fma_f32 v13, -v16, v12, v6
	v_fmac_f32_e32 v12, v13, v17
	v_mul_f32_e32 v13, 0xbfb8aa3b, v8
	v_exp_f32_e32 v13, v13
	v_fma_f32 v6, -v16, v12, v6
	v_div_fmas_f32 v6, v6, v17, v12
	v_div_fixup_f32 v6, v6, v15, v7
	v_add_f32_e32 v13, 1.0, v13
	v_div_scale_f32 v14, s[10:11], v13, v13, v8
	v_rcp_f32_e32 v16, v14
	v_mul_f32_e32 v3, v6, v3
	v_mul_f32_e32 v6, 0xbfb8aa3b, v9
	v_exp_f32_e32 v6, v6
	v_cvt_pk_bf16_f32 v12, v2, v3
	v_fma_f32 v2, -v14, v16, 1.0
	v_fmac_f32_e32 v16, v2, v16
	v_div_scale_f32 v2, vcc, v8, v13, v8
	v_mul_f32_e32 v3, v2, v16
	v_fma_f32 v7, -v14, v3, v2
	v_add_f32_e32 v6, 1.0, v6
	v_fmac_f32_e32 v3, v7, v16
	v_div_scale_f32 v7, s[10:11], v6, v6, v9
	v_fma_f32 v2, -v14, v3, v2
	v_rcp_f32_e32 v14, v7
	v_div_fmas_f32 v2, v2, v16, v3
	v_div_fixup_f32 v2, v2, v13, v8
	v_mul_f32_e32 v2, v2, v4
	v_fma_f32 v3, -v7, v14, 1.0
	v_fmac_f32_e32 v14, v3, v14
	v_div_scale_f32 v3, vcc, v9, v6, v9
	v_mul_f32_e32 v4, v3, v14
	v_fma_f32 v8, -v7, v4, v3
	v_fmac_f32_e32 v4, v8, v14
	v_fma_f32 v3, -v7, v4, v3
	v_div_fmas_f32 v3, v3, v14, v4
	v_div_fixup_f32 v3, v3, v6, v9
	v_mul_f32_e32 v3, v3, v5
	v_add_u32_e32 v1, 0x40b0, v1
	v_cvt_pk_bf16_f32 v13, v2, v3
	v_mad_i64_i32 v[2:3], s[8:9], v1, s8, v[114:115]
	v_lshl_add_u64 v[2:3], v[2:3], 0, v[116:117]
	global_store_dwordx4 v[2:3], v[10:13], off
	s_waitcnt vmcnt(0)
	s_barrier
	s_waitcnt vmcnt(0)
	s_waitcnt vmcnt(0) lgkmcnt(0)
	s_barrier
	s_mov_b64 s[8:9], exec
	v_readlane_b32 s10, v228, 2
	v_readlane_b32 s11, v228, 3
	s_and_b64 s[10:11], s[8:9], s[10:11]
	s_mov_b64 exec, s[10:11]
	s_cbranch_execz .LBB0_800
	s_mov_b64 s[10:11], exec
	v_mbcnt_lo_u32_b32 v1, s10, 0
	buffer_wbl2 sc1
	s_waitcnt vmcnt(0)
	v_mbcnt_hi_u32_b32 v1, s11, v1
	v_cmp_eq_u32_e32 vcc, 0, v1
	s_and_b64 s[18:19], exec, vcc
	s_mov_b64 exec, s[18:19]
	s_cbranch_execz .LBB0_800
	s_bcnt1_i32_b64 s10, s[10:11]
	v_mov_b32_e32 v1, 0
	v_mov_b32_e32 v2, s10
	global_atomic_add v1, v2, s[6:7]

.LBB0_816:
	s_add_u32 s6, s38, 0x7800000
	s_addc_u32 s7, s39, 0
	s_lshl_b32 s9, s24, 8
	s_add_i32 s8, s13, 0x4000
	v_lshl_or_b32 v131, v131, 2, s9
	v_or_b32_e32 v138, s35, v131
	v_or_b32_e32 v142, s8, v1
	s_movk_i32 s11, 0x4080
	s_movk_i32 s18, 0x4000
	s_ashr_i32 s10, s8, 13
	v_cmp_gt_i32_e32 vcc, s11, v142
	v_or_b32_e32 v140, 16, v138
	s_and_saveexec_b64 s[8:9], vcc
	s_cbranch_execz .LBB0_818
	v_add_u32_e32 v131, 0xffffc002, v142
	v_mov_b32_e32 v133, s10
	v_cmp_gt_i32_e32 vcc, s18, v142
	s_mov_b32 s18, 0x9000
	v_mov_b64_e32 v[144:145], s[42:43]
	v_cndmask_b32_e32 v131, v131, v133, vcc
	v_mad_i64_i32 v[144:145], s[18:19], v131, s18, v[144:145]
	v_ashrrev_i32_e32 v143, 31, v142
	v_add_u32_e32 v158, 0xffffc000, v142
	v_mov_b32_e32 v159, 0
	s_mov_b64 s[18:19], 0x2000
	v_lshlrev_b64 v[152:153], 12, v[142:143]
	v_lshlrev_b64 v[146:147], 12, v[158:159]
	v_mov_b32_e32 v139, v159
	v_lshl_add_u64 v[156:157], v[144:145], 0, s[18:19]
	v_lshl_add_u64 v[144:145], v[134:135], 0, v[152:153]
	v_lshl_add_u64 v[146:147], v[136:137], 0, v[146:147]
	v_lshlrev_b64 v[154:155], 2, v[138:139]
	v_cndmask_b32_e32 v149, v147, v145, vcc
	v_cndmask_b32_e32 v148, v146, v144, vcc
	v_lshl_add_u64 v[144:145], v[156:157], 0, v[154:155]
	global_load_dwordx4 v[144:147], v[144:145], off
	v_lshl_add_u64 v[160:161], v[148:149], 0, v[154:155]
	global_load_dwordx4 v[148:151], v[160:161], off
	v_mov_b32_e32 v141, v159
	v_lshl_add_u64 v[152:153], s[6:7], 0, v[152:153]
	v_lshl_add_u64 v[162:163], v[152:153], 0, v[154:155]
	v_lshl_add_u64 v[152:153], v[140:141], 2, v[156:157]
	global_load_dwordx4 v[152:155], v[152:153], off
	v_or_b32_e32 v158, 0x80, v138
	s_waitcnt vmcnt(0) lgkmcnt(0)
	v_pk_mul_f32 v[128:129], v[128:129], v[146:147]
	v_pk_mul_f32 v[126:127], v[126:127], v[144:145]
	v_pk_fma_f32 v[128:129], v[128:129], 0.5, v[150:151] op_sel_hi:[1,0,1]
	v_pk_fma_f32 v[126:127], v[126:127], 0.5, v[148:149] op_sel_hi:[1,0,1]
	global_store_dwordx4 v[162:163], v[126:129], off
	global_load_dwordx4 v[126:129], v[160:161], off offset:64
	v_lshl_add_u64 v[144:145], v[158:159], 2, v[156:157]
	v_pk_mul_f32 v[124:125], v[124:125], v[154:155]
	v_pk_mul_f32 v[122:123], v[122:123], v[152:153]
	global_load_dwordx4 v[144:147], v[144:145], off
	v_or_b32_e32 v158, 0x90, v138
	s_waitcnt vmcnt(0)
	v_pk_fma_f32 v[124:125], v[124:125], 0.5, v[128:129] op_sel_hi:[1,0,1]
	v_pk_fma_f32 v[122:123], v[122:123], 0.5, v[126:127] op_sel_hi:[1,0,1]
	global_store_dwordx4 v[162:163], v[122:125], off offset:64
	global_load_dwordx4 v[122:125], v[160:161], off offset:512
	v_lshl_add_u64 v[126:127], v[158:159], 2, v[156:157]
	global_load_dwordx4 v[126:129], v[126:127], off
	s_waitcnt lgkmcnt(0)
	v_pk_mul_f32 v[120:121], v[120:121], v[146:147]
	v_pk_mul_f32 v[118:119], v[118:119], v[144:145]
	s_waitcnt vmcnt(0)
	v_pk_fma_f32 v[120:121], v[120:121], 0.5, v[124:125] op_sel_hi:[1,0,1]
	v_pk_fma_f32 v[118:119], v[118:119], 0.5, v[122:123] op_sel_hi:[1,0,1]
	global_store_dwordx4 v[162:163], v[118:121], off offset:512
	global_load_dwordx4 v[118:121], v[160:161], off offset:576
	v_pk_mul_f32 v[116:117], v[116:117], v[128:129]
	v_pk_mul_f32 v[114:115], v[114:115], v[126:127]
	s_waitcnt vmcnt(0)
	v_pk_fma_f32 v[116:117], v[116:117], 0.5, v[120:121] op_sel_hi:[1,0,1]
	v_pk_fma_f32 v[114:115], v[114:115], 0.5, v[118:119] op_sel_hi:[1,0,1]
	global_store_dwordx4 v[162:163], v[114:117], off offset:576
.LBB0_818:
	s_or_b64 exec, exec, s[8:9]
	s_nop 0
	v_or_b32_e32 v114, 16, v142
	v_cmp_gt_i32_e32 vcc, s11, v114
	s_and_saveexec_b64 s[8:9], vcc
	s_cbranch_execz .LBB0_820
	s_movk_i32 s11, 0x4000
	v_add_u32_e32 v115, 0xffffc012, v142
	v_mov_b32_e32 v116, s10
	v_cmp_gt_i32_e32 vcc, s11, v114
	s_mov_b32 s11, 0x9000
	v_add_u32_e32 v128, 0xffffc010, v142
	v_cndmask_b32_e32 v115, v115, v116, vcc
	v_mov_b64_e32 v[116:117], s[42:43]
	v_mad_i64_i32 v[116:117], s[18:19], v115, s11, v[116:117]
	s_mov_b64 s[18:19], 0x2000
	v_ashrrev_i32_e32 v115, 31, v114
	v_mov_b32_e32 v129, 0
	v_lshl_add_u64 v[126:127], v[116:117], 0, s[18:19]
	v_lshlrev_b64 v[122:123], 12, v[114:115]
	v_lshlrev_b64 v[116:117], 12, v[128:129]
	v_mov_b32_e32 v139, v129
	v_lshl_add_u64 v[114:115], v[134:135], 0, v[122:123]
	v_lshl_add_u64 v[116:117], v[136:137], 0, v[116:117]
	v_lshlrev_b64 v[124:125], 2, v[138:139]
	v_cndmask_b32_e32 v119, v117, v115, vcc
	v_cndmask_b32_e32 v118, v116, v114, vcc
	v_lshl_add_u64 v[114:115], v[126:127], 0, v[124:125]
	global_load_dwordx4 v[114:117], v[114:115], off
	v_lshl_add_u64 v[144:145], v[118:119], 0, v[124:125]
	global_load_dwordx4 v[118:121], v[144:145], off
	v_mov_b32_e32 v141, v129
	v_lshl_add_u64 v[122:123], s[6:7], 0, v[122:123]
	v_lshl_add_u64 v[146:147], v[122:123], 0, v[124:125]
	v_lshl_add_u64 v[122:123], v[140:141], 2, v[126:127]
	global_load_dwordx4 v[122:125], v[122:123], off
	v_or_b32_e32 v128, 0x80, v138
	s_waitcnt vmcnt(0) lgkmcnt(0)
	v_pk_mul_f32 v[112:113], v[112:113], v[116:117]
	v_pk_mul_f32 v[110:111], v[110:111], v[114:115]
	v_pk_fma_f32 v[112:113], v[112:113], 0.5, v[120:121] op_sel_hi:[1,0,1]
	v_pk_fma_f32 v[110:111], v[110:111], 0.5, v[118:119] op_sel_hi:[1,0,1]
	global_store_dwordx4 v[146:147], v[110:113], off
	global_load_dwordx4 v[110:113], v[144:145], off offset:64
	v_lshl_add_u64 v[114:115], v[128:129], 2, v[126:127]
	v_pk_mul_f32 v[108:109], v[108:109], v[124:125]
	v_pk_mul_f32 v[106:107], v[106:107], v[122:123]
	global_load_dwordx4 v[114:117], v[114:115], off
	v_or_b32_e32 v128, 0x90, v138
	s_waitcnt vmcnt(0)
	v_pk_fma_f32 v[108:109], v[108:109], 0.5, v[112:113] op_sel_hi:[1,0,1]
	v_pk_fma_f32 v[106:107], v[106:107], 0.5, v[110:111] op_sel_hi:[1,0,1]
	global_store_dwordx4 v[146:147], v[106:109], off offset:64
	global_load_dwordx4 v[106:109], v[144:145], off offset:512
	v_lshl_add_u64 v[110:111], v[128:129], 2, v[126:127]
	global_load_dwordx4 v[110:113], v[110:111], off
	s_waitcnt lgkmcnt(0)
	v_pk_mul_f32 v[104:105], v[104:105], v[116:117]
	v_pk_mul_f32 v[102:103], v[102:103], v[114:115]
	s_waitcnt vmcnt(0)
	v_pk_fma_f32 v[104:105], v[104:105], 0.5, v[108:109] op_sel_hi:[1,0,1]
	v_pk_fma_f32 v[102:103], v[102:103], 0.5, v[106:107] op_sel_hi:[1,0,1]
	global_store_dwordx4 v[146:147], v[102:105], off offset:512
	global_load_dwordx4 v[102:105], v[144:145], off offset:576
	v_pk_mul_f32 v[100:101], v[100:101], v[112:113]
	v_pk_mul_f32 v[98:99], v[98:99], v[110:111]
	s_waitcnt vmcnt(0)
	v_pk_fma_f32 v[100:101], v[100:101], 0.5, v[104:105] op_sel_hi:[1,0,1]
	v_pk_fma_f32 v[98:99], v[98:99], 0.5, v[102:103] op_sel_hi:[1,0,1]
	global_store_dwordx4 v[146:147], v[98:101], off offset:576
.LBB0_820:
	s_or_b64 exec, exec, s[8:9]
	s_nop 0
	v_or_b32_e32 v98, 32, v142
	s_movk_i32 s11, 0x4080
	v_cmp_gt_i32_e32 vcc, s11, v98
	s_and_saveexec_b64 s[8:9], vcc
	s_cbranch_execz .LBB0_822
	s_movk_i32 s18, 0x4000
	v_add_u32_e32 v99, 0xffffc022, v142
	v_mov_b32_e32 v100, s10
	v_cmp_gt_i32_e32 vcc, s18, v98
	s_mov_b32 s18, 0x9000
	v_add_u32_e32 v112, 0xffffc020, v142
	v_cndmask_b32_e32 v99, v99, v100, vcc
	v_mov_b64_e32 v[100:101], s[42:43]
	v_mad_i64_i32 v[100:101], s[18:19], v99, s18, v[100:101]
	s_mov_b64 s[18:19], 0x2000
	v_ashrrev_i32_e32 v99, 31, v98
	v_mov_b32_e32 v113, 0
	v_lshl_add_u64 v[110:111], v[100:101], 0, s[18:19]
	v_lshlrev_b64 v[106:107], 12, v[98:99]
	v_lshlrev_b64 v[100:101], 12, v[112:113]
	v_mov_b32_e32 v139, v113
	v_lshl_add_u64 v[98:99], v[134:135], 0, v[106:107]
	v_lshl_add_u64 v[100:101], v[136:137], 0, v[100:101]
	v_lshlrev_b64 v[108:109], 2, v[138:139]
	v_cndmask_b32_e32 v103, v101, v99, vcc
	v_cndmask_b32_e32 v102, v100, v98, vcc
	v_lshl_add_u64 v[98:99], v[110:111], 0, v[108:109]
	global_load_dwordx4 v[98:101], v[98:99], off
	v_lshl_add_u64 v[114:115], v[102:103], 0, v[108:109]
	global_load_dwordx4 v[102:105], v[114:115], off
	v_mov_b32_e32 v141, v113
	v_lshl_add_u64 v[106:107], s[6:7], 0, v[106:107]
	v_lshl_add_u64 v[116:117], v[106:107], 0, v[108:109]
	v_lshl_add_u64 v[106:107], v[140:141], 2, v[110:111]
	global_load_dwordx4 v[106:109], v[106:107], off
	v_or_b32_e32 v112, 0x80, v138
	s_waitcnt vmcnt(0) lgkmcnt(0)
	v_pk_mul_f32 v[96:97], v[96:97], v[100:101]
	v_pk_mul_f32 v[94:95], v[94:95], v[98:99]
	v_pk_fma_f32 v[96:97], v[96:97], 0.5, v[104:105] op_sel_hi:[1,0,1]
	v_pk_fma_f32 v[94:95], v[94:95], 0.5, v[102:103] op_sel_hi:[1,0,1]
	global_store_dwordx4 v[116:117], v[94:97], off
	global_load_dwordx4 v[94:97], v[114:115], off offset:64
	v_lshl_add_u64 v[98:99], v[112:113], 2, v[110:111]
	v_pk_mul_f32 v[92:93], v[92:93], v[108:109]
	v_pk_mul_f32 v[90:91], v[90:91], v[106:107]
	global_load_dwordx4 v[98:101], v[98:99], off
	v_or_b32_e32 v112, 0x90, v138
	s_waitcnt vmcnt(0)
	v_pk_fma_f32 v[92:93], v[92:93], 0.5, v[96:97] op_sel_hi:[1,0,1]
	v_pk_fma_f32 v[90:91], v[90:91], 0.5, v[94:95] op_sel_hi:[1,0,1]
	global_store_dwordx4 v[116:117], v[90:93], off offset:64
	global_load_dwordx4 v[90:93], v[114:115], off offset:512
	v_lshl_add_u64 v[94:95], v[112:113], 2, v[110:111]
	global_load_dwordx4 v[94:97], v[94:95], off
	s_waitcnt lgkmcnt(0)
	v_pk_mul_f32 v[88:89], v[88:89], v[100:101]
	v_pk_mul_f32 v[86:87], v[86:87], v[98:99]
	s_waitcnt vmcnt(0)
	v_pk_fma_f32 v[88:89], v[88:89], 0.5, v[92:93] op_sel_hi:[1,0,1]
	v_pk_fma_f32 v[86:87], v[86:87], 0.5, v[90:91] op_sel_hi:[1,0,1]
	global_store_dwordx4 v[116:117], v[86:89], off offset:512
	global_load_dwordx4 v[86:89], v[114:115], off offset:576
	v_pk_mul_f32 v[84:85], v[84:85], v[96:97]
	v_pk_mul_f32 v[82:83], v[82:83], v[94:95]
	s_waitcnt vmcnt(0)
	v_pk_fma_f32 v[84:85], v[84:85], 0.5, v[88:89] op_sel_hi:[1,0,1]
	v_pk_fma_f32 v[82:83], v[82:83], 0.5, v[86:87] op_sel_hi:[1,0,1]
	global_store_dwordx4 v[116:117], v[82:85], off offset:576
.LBB0_822:
	s_or_b64 exec, exec, s[8:9]
	s_nop 0
	v_or_b32_e32 v82, 48, v142
	v_cmp_gt_i32_e32 vcc, s11, v82
	s_and_saveexec_b64 s[8:9], vcc
	s_cbranch_execz .LBB0_824
	s_movk_i32 s11, 0x4000
	v_add_u32_e32 v83, 0xffffc032, v142
	v_mov_b32_e32 v84, s10
	v_cmp_gt_i32_e32 vcc, s11, v82
	s_mov_b32 s10, 0x9000
	v_add_u32_e32 v96, 0xffffc030, v142
	v_cndmask_b32_e32 v83, v83, v84, vcc
	v_mov_b64_e32 v[84:85], s[42:43]
	v_mad_i64_i32 v[84:85], s[10:11], v83, s10, v[84:85]
	s_mov_b64 s[10:11], 0x2000
	v_ashrrev_i32_e32 v83, 31, v82
	v_mov_b32_e32 v97, 0
	v_lshl_add_u64 v[94:95], v[84:85], 0, s[10:11]
	v_lshlrev_b64 v[90:91], 12, v[82:83]
	v_lshlrev_b64 v[84:85], 12, v[96:97]
	v_mov_b32_e32 v139, v97
	v_lshl_add_u64 v[82:83], v[134:135], 0, v[90:91]
	v_lshl_add_u64 v[84:85], v[136:137], 0, v[84:85]
	v_lshlrev_b64 v[92:93], 2, v[138:139]
	v_cndmask_b32_e32 v87, v85, v83, vcc
	v_cndmask_b32_e32 v86, v84, v82, vcc
	v_lshl_add_u64 v[82:83], v[94:95], 0, v[92:93]
	global_load_dwordx4 v[82:85], v[82:83], off
	v_lshl_add_u64 v[98:99], v[86:87], 0, v[92:93]
	global_load_dwordx4 v[86:89], v[98:99], off
	v_mov_b32_e32 v141, v97
	v_lshl_add_u64 v[90:91], s[6:7], 0, v[90:91]
	v_lshl_add_u64 v[100:101], v[90:91], 0, v[92:93]
	v_lshl_add_u64 v[90:91], v[140:141], 2, v[94:95]
	global_load_dwordx4 v[90:93], v[90:91], off
	v_or_b32_e32 v96, 0x80, v138
	s_waitcnt vmcnt(0) lgkmcnt(0)
	v_pk_mul_f32 v[80:81], v[80:81], v[84:85]
	v_pk_mul_f32 v[78:79], v[78:79], v[82:83]
	v_pk_fma_f32 v[80:81], v[80:81], 0.5, v[88:89] op_sel_hi:[1,0,1]
	v_pk_fma_f32 v[78:79], v[78:79], 0.5, v[86:87] op_sel_hi:[1,0,1]
	global_store_dwordx4 v[100:101], v[78:81], off
	global_load_dwordx4 v[78:81], v[98:99], off offset:64
	v_lshl_add_u64 v[82:83], v[96:97], 2, v[94:95]
	v_pk_mul_f32 v[76:77], v[76:77], v[92:93]
	v_pk_mul_f32 v[74:75], v[74:75], v[90:91]
	global_load_dwordx4 v[82:85], v[82:83], off
	v_or_b32_e32 v96, 0x90, v138
	s_waitcnt vmcnt(0)
	v_pk_fma_f32 v[76:77], v[76:77], 0.5, v[80:81] op_sel_hi:[1,0,1]
	v_pk_fma_f32 v[74:75], v[74:75], 0.5, v[78:79] op_sel_hi:[1,0,1]
	global_store_dwordx4 v[100:101], v[74:77], off offset:64
	global_load_dwordx4 v[74:77], v[98:99], off offset:512
	v_lshl_add_u64 v[78:79], v[96:97], 2, v[94:95]
	global_load_dwordx4 v[78:81], v[78:79], off
	s_waitcnt lgkmcnt(0)
	v_pk_mul_f32 v[72:73], v[72:73], v[84:85]
	v_pk_mul_f32 v[70:71], v[70:71], v[82:83]
	s_waitcnt vmcnt(0)
	v_pk_fma_f32 v[72:73], v[72:73], 0.5, v[76:77] op_sel_hi:[1,0,1]
	v_pk_fma_f32 v[70:71], v[70:71], 0.5, v[74:75] op_sel_hi:[1,0,1]
	global_store_dwordx4 v[100:101], v[70:73], off offset:512
	global_load_dwordx4 v[70:73], v[98:99], off offset:576
	v_pk_mul_f32 v[68:69], v[68:69], v[80:81]
	v_pk_mul_f32 v[66:67], v[66:67], v[78:79]
	s_waitcnt vmcnt(0)
	v_pk_fma_f32 v[68:69], v[68:69], 0.5, v[72:73] op_sel_hi:[1,0,1]
	v_pk_fma_f32 v[66:67], v[66:67], 0.5, v[70:71] op_sel_hi:[1,0,1]
	global_store_dwordx4 v[100:101], v[66:69], off offset:576
.LBB0_824:
	s_or_b64 exec, exec, s[8:9]
	s_addk_i32 s13, 0x4080
	s_movk_i32 s11, 0x4080
	v_or_b32_e32 v66, s13, v1
	s_ashr_i32 s10, s13, 13
	v_cmp_gt_i32_e32 vcc, s11, v66
	s_and_saveexec_b64 s[8:9], vcc
	s_cbranch_execz .LBB0_826
	s_movk_i32 s13, 0x4000
	v_add_u32_e32 v1, 0xffffc002, v66
	v_mov_b32_e32 v67, s10
	v_cmp_gt_i32_e32 vcc, s13, v66
	s_mov_b32 s13, 0x9000
	v_mov_b64_e32 v[68:69], s[42:43]
	v_cndmask_b32_e32 v1, v1, v67, vcc
	v_mad_i64_i32 v[68:69], s[18:19], v1, s13, v[68:69]
	v_ashrrev_i32_e32 v67, 31, v66
	v_add_u32_e32 v82, 0xffffc000, v66
	v_mov_b32_e32 v83, 0
	s_mov_b64 s[18:19], 0x2000
	v_lshlrev_b64 v[76:77], 12, v[66:67]
	v_lshlrev_b64 v[70:71], 12, v[82:83]
	v_mov_b32_e32 v139, v83
	v_lshl_add_u64 v[80:81], v[68:69], 0, s[18:19]
	v_lshl_add_u64 v[68:69], v[134:135], 0, v[76:77]
	v_lshl_add_u64 v[70:71], v[136:137], 0, v[70:71]
	v_lshlrev_b64 v[78:79], 2, v[138:139]
	v_cndmask_b32_e32 v73, v71, v69, vcc
	v_cndmask_b32_e32 v72, v70, v68, vcc
	v_lshl_add_u64 v[68:69], v[80:81], 0, v[78:79]
	global_load_dwordx4 v[68:71], v[68:69], off
	v_lshl_add_u64 v[84:85], v[72:73], 0, v[78:79]
	global_load_dwordx4 v[72:75], v[84:85], off
	v_mov_b32_e32 v141, v83
	v_lshl_add_u64 v[76:77], s[6:7], 0, v[76:77]
	v_lshl_add_u64 v[86:87], v[76:77], 0, v[78:79]
	v_lshl_add_u64 v[76:77], v[140:141], 2, v[80:81]
	global_load_dwordx4 v[76:79], v[76:77], off
	v_or_b32_e32 v82, 0x80, v138
	s_waitcnt vmcnt(0) lgkmcnt(0)
	v_pk_mul_f32 v[64:65], v[64:65], v[70:71]
	v_pk_mul_f32 v[62:63], v[62:63], v[68:69]
	v_pk_fma_f32 v[64:65], v[64:65], 0.5, v[74:75] op_sel_hi:[1,0,1]
	v_pk_fma_f32 v[62:63], v[62:63], 0.5, v[72:73] op_sel_hi:[1,0,1]
	global_store_dwordx4 v[86:87], v[62:65], off
	global_load_dwordx4 v[62:65], v[84:85], off offset:64
	v_lshl_add_u64 v[68:69], v[82:83], 2, v[80:81]
	v_pk_mul_f32 v[60:61], v[60:61], v[78:79]
	v_pk_mul_f32 v[58:59], v[58:59], v[76:77]
	global_load_dwordx4 v[68:71], v[68:69], off
	v_or_b32_e32 v82, 0x90, v138
	s_waitcnt vmcnt(0)
	v_pk_fma_f32 v[60:61], v[60:61], 0.5, v[64:65] op_sel_hi:[1,0,1]
	v_pk_fma_f32 v[58:59], v[58:59], 0.5, v[62:63] op_sel_hi:[1,0,1]
	global_store_dwordx4 v[86:87], v[58:61], off offset:64
	global_load_dwordx4 v[58:61], v[84:85], off offset:512
	v_lshl_add_u64 v[62:63], v[82:83], 2, v[80:81]
	global_load_dwordx4 v[62:65], v[62:63], off
	s_waitcnt lgkmcnt(0)
	v_pk_mul_f32 v[56:57], v[56:57], v[70:71]
	v_pk_mul_f32 v[54:55], v[54:55], v[68:69]
	s_waitcnt vmcnt(0)
	v_pk_fma_f32 v[56:57], v[56:57], 0.5, v[60:61] op_sel_hi:[1,0,1]
	v_pk_fma_f32 v[54:55], v[54:55], 0.5, v[58:59] op_sel_hi:[1,0,1]
	global_store_dwordx4 v[86:87], v[54:57], off offset:512
	global_load_dwordx4 v[54:57], v[84:85], off offset:576
	v_pk_mul_f32 v[52:53], v[52:53], v[64:65]
	v_pk_mul_f32 v[50:51], v[50:51], v[62:63]
	s_waitcnt vmcnt(0)
	v_pk_fma_f32 v[52:53], v[52:53], 0.5, v[56:57] op_sel_hi:[1,0,1]
	v_pk_fma_f32 v[50:51], v[50:51], 0.5, v[54:55] op_sel_hi:[1,0,1]
	global_store_dwordx4 v[86:87], v[50:53], off offset:576
.LBB0_826:
	s_or_b64 exec, exec, s[8:9]
	s_nop 0
	v_or_b32_e32 v50, 16, v66
	v_cmp_gt_i32_e32 vcc, s11, v50
	s_and_saveexec_b64 s[8:9], vcc
	s_cbranch_execz .LBB0_828
	s_movk_i32 s11, 0x4000
	v_add_u32_e32 v1, 0xffffc012, v66
	v_mov_b32_e32 v51, s10
	v_cmp_gt_i32_e32 vcc, s11, v50
	s_mov_b32 s11, 0x9000
	v_mov_b64_e32 v[52:53], s[42:43]
	v_cndmask_b32_e32 v1, v1, v51, vcc
	v_mad_i64_i32 v[52:53], s[18:19], v1, s11, v[52:53]
	s_mov_b64 s[18:19], 0x2000
	v_ashrrev_i32_e32 v51, 31, v50
	v_add_u32_e32 v64, 0xffffc010, v66
	v_mov_b32_e32 v65, 0
	v_lshl_add_u64 v[62:63], v[52:53], 0, s[18:19]
	v_lshlrev_b64 v[58:59], 12, v[50:51]
	v_lshlrev_b64 v[52:53], 12, v[64:65]
	v_mov_b32_e32 v139, v65
	v_lshl_add_u64 v[50:51], v[134:135], 0, v[58:59]
	v_lshl_add_u64 v[52:53], v[136:137], 0, v[52:53]
	v_lshlrev_b64 v[60:61], 2, v[138:139]
	v_cndmask_b32_e32 v55, v53, v51, vcc
	v_cndmask_b32_e32 v54, v52, v50, vcc
	v_lshl_add_u64 v[50:51], v[62:63], 0, v[60:61]
	global_load_dwordx4 v[50:53], v[50:51], off
	v_lshl_add_u64 v[68:69], v[54:55], 0, v[60:61]
	global_load_dwordx4 v[54:57], v[68:69], off
	v_mov_b32_e32 v141, v65
	v_lshl_add_u64 v[58:59], s[6:7], 0, v[58:59]
	v_lshl_add_u64 v[70:71], v[58:59], 0, v[60:61]
	v_lshl_add_u64 v[58:59], v[140:141], 2, v[62:63]
	global_load_dwordx4 v[58:61], v[58:59], off
	v_or_b32_e32 v64, 0x80, v138
	s_waitcnt vmcnt(0) lgkmcnt(0)
	v_pk_mul_f32 v[48:49], v[48:49], v[52:53]
	v_pk_mul_f32 v[46:47], v[46:47], v[50:51]
	v_pk_fma_f32 v[48:49], v[48:49], 0.5, v[56:57] op_sel_hi:[1,0,1]
	v_pk_fma_f32 v[46:47], v[46:47], 0.5, v[54:55] op_sel_hi:[1,0,1]
	global_store_dwordx4 v[70:71], v[46:49], off
	global_load_dwordx4 v[46:49], v[68:69], off offset:64
	v_lshl_add_u64 v[50:51], v[64:65], 2, v[62:63]
	v_pk_mul_f32 v[44:45], v[44:45], v[60:61]
	v_pk_mul_f32 v[42:43], v[42:43], v[58:59]
	global_load_dwordx4 v[50:53], v[50:51], off
	v_or_b32_e32 v64, 0x90, v138
	s_waitcnt vmcnt(0)
	v_pk_fma_f32 v[44:45], v[44:45], 0.5, v[48:49] op_sel_hi:[1,0,1]
	v_pk_fma_f32 v[42:43], v[42:43], 0.5, v[46:47] op_sel_hi:[1,0,1]
	global_store_dwordx4 v[70:71], v[42:45], off offset:64
	global_load_dwordx4 v[42:45], v[68:69], off offset:512
	v_lshl_add_u64 v[46:47], v[64:65], 2, v[62:63]
	global_load_dwordx4 v[46:49], v[46:47], off
	s_waitcnt lgkmcnt(0)
	v_pk_mul_f32 v[40:41], v[40:41], v[52:53]
	v_pk_mul_f32 v[38:39], v[38:39], v[50:51]
	s_waitcnt vmcnt(0)
	v_pk_fma_f32 v[40:41], v[40:41], 0.5, v[44:45] op_sel_hi:[1,0,1]
	v_pk_fma_f32 v[38:39], v[38:39], 0.5, v[42:43] op_sel_hi:[1,0,1]
	global_store_dwordx4 v[70:71], v[38:41], off offset:512
	global_load_dwordx4 v[38:41], v[68:69], off offset:576
	v_pk_mul_f32 v[36:37], v[36:37], v[48:49]
	v_pk_mul_f32 v[34:35], v[34:35], v[46:47]
	s_waitcnt vmcnt(0)
	v_pk_fma_f32 v[36:37], v[36:37], 0.5, v[40:41] op_sel_hi:[1,0,1]
	v_pk_fma_f32 v[34:35], v[34:35], 0.5, v[38:39] op_sel_hi:[1,0,1]
	global_store_dwordx4 v[70:71], v[34:37], off offset:576
.LBB0_828:
	s_or_b64 exec, exec, s[8:9]
	s_nop 0
	v_or_b32_e32 v34, 32, v66
	s_movk_i32 s11, 0x4080
	v_cmp_gt_i32_e32 vcc, s11, v34
	s_and_saveexec_b64 s[8:9], vcc
	s_cbranch_execz .LBB0_830
	s_movk_i32 s13, 0x4000
	v_add_u32_e32 v1, 0xffffc022, v66
	v_mov_b32_e32 v35, s10
	v_cmp_gt_i32_e32 vcc, s13, v34
	s_mov_b32 s13, 0x9000
	v_mov_b64_e32 v[36:37], s[42:43]
	v_cndmask_b32_e32 v1, v1, v35, vcc
	v_mad_i64_i32 v[36:37], s[18:19], v1, s13, v[36:37]
	s_mov_b64 s[18:19], 0x2000
	v_ashrrev_i32_e32 v35, 31, v34
	v_add_u32_e32 v48, 0xffffc020, v66
	v_mov_b32_e32 v49, 0
	v_lshl_add_u64 v[46:47], v[36:37], 0, s[18:19]
	v_lshlrev_b64 v[42:43], 12, v[34:35]
	v_lshlrev_b64 v[36:37], 12, v[48:49]
	v_mov_b32_e32 v139, v49
	v_lshl_add_u64 v[34:35], v[134:135], 0, v[42:43]
	v_lshl_add_u64 v[36:37], v[136:137], 0, v[36:37]
	v_lshlrev_b64 v[44:45], 2, v[138:139]
	v_cndmask_b32_e32 v39, v37, v35, vcc
	v_cndmask_b32_e32 v38, v36, v34, vcc
	v_lshl_add_u64 v[34:35], v[46:47], 0, v[44:45]
	global_load_dwordx4 v[34:37], v[34:35], off
	v_lshl_add_u64 v[50:51], v[38:39], 0, v[44:45]
	global_load_dwordx4 v[38:41], v[50:51], off
	v_mov_b32_e32 v141, v49
	v_lshl_add_u64 v[42:43], s[6:7], 0, v[42:43]
	v_lshl_add_u64 v[52:53], v[42:43], 0, v[44:45]
	v_lshl_add_u64 v[42:43], v[140:141], 2, v[46:47]
	global_load_dwordx4 v[42:45], v[42:43], off
	v_or_b32_e32 v48, 0x80, v138
	s_waitcnt vmcnt(0) lgkmcnt(0)
	v_pk_mul_f32 v[32:33], v[32:33], v[36:37]
	v_pk_mul_f32 v[30:31], v[30:31], v[34:35]
	v_pk_fma_f32 v[32:33], v[32:33], 0.5, v[40:41] op_sel_hi:[1,0,1]
	v_pk_fma_f32 v[30:31], v[30:31], 0.5, v[38:39] op_sel_hi:[1,0,1]
	global_store_dwordx4 v[52:53], v[30:33], off
	global_load_dwordx4 v[30:33], v[50:51], off offset:64
	v_lshl_add_u64 v[34:35], v[48:49], 2, v[46:47]
	v_pk_mul_f32 v[28:29], v[28:29], v[44:45]
	v_pk_mul_f32 v[26:27], v[26:27], v[42:43]
	global_load_dwordx4 v[34:37], v[34:35], off
	v_or_b32_e32 v48, 0x90, v138
	s_waitcnt vmcnt(0)
	v_pk_fma_f32 v[28:29], v[28:29], 0.5, v[32:33] op_sel_hi:[1,0,1]
	v_pk_fma_f32 v[26:27], v[26:27], 0.5, v[30:31] op_sel_hi:[1,0,1]
	global_store_dwordx4 v[52:53], v[26:29], off offset:64
	global_load_dwordx4 v[26:29], v[50:51], off offset:512
	v_lshl_add_u64 v[30:31], v[48:49], 2, v[46:47]
	global_load_dwordx4 v[30:33], v[30:31], off
	s_waitcnt lgkmcnt(0)
	v_pk_mul_f32 v[24:25], v[24:25], v[36:37]
	v_pk_mul_f32 v[22:23], v[22:23], v[34:35]
	s_waitcnt vmcnt(0)
	v_pk_fma_f32 v[24:25], v[24:25], 0.5, v[28:29] op_sel_hi:[1,0,1]
	v_pk_fma_f32 v[22:23], v[22:23], 0.5, v[26:27] op_sel_hi:[1,0,1]
	global_store_dwordx4 v[52:53], v[22:25], off offset:512
	global_load_dwordx4 v[22:25], v[50:51], off offset:576
	v_pk_mul_f32 v[20:21], v[20:21], v[32:33]
	v_pk_mul_f32 v[18:19], v[18:19], v[30:31]
	s_waitcnt vmcnt(0)
	v_pk_fma_f32 v[20:21], v[20:21], 0.5, v[24:25] op_sel_hi:[1,0,1]
	v_pk_fma_f32 v[18:19], v[18:19], 0.5, v[22:23] op_sel_hi:[1,0,1]
	global_store_dwordx4 v[52:53], v[18:21], off offset:576
.LBB0_830:
	s_or_b64 exec, exec, s[8:9]
	s_nop 0
	v_or_b32_e32 v18, 48, v66
	v_cmp_gt_i32_e32 vcc, s11, v18
	s_and_saveexec_b64 s[8:9], vcc
	s_cbranch_execz .LBB0_832
	s_movk_i32 s11, 0x4000
	v_add_u32_e32 v1, 0xffffc032, v66
	v_mov_b32_e32 v19, s10
	v_cmp_gt_i32_e32 vcc, s11, v18
	s_mov_b32 s10, 0x9000
	v_mov_b64_e32 v[20:21], s[42:43]
	v_cndmask_b32_e32 v1, v1, v19, vcc
	v_mad_i64_i32 v[20:21], s[10:11], v1, s10, v[20:21]
	s_mov_b64 s[10:11], 0x2000
	v_ashrrev_i32_e32 v19, 31, v18
	v_add_u32_e32 v32, 0xffffc030, v66
	v_mov_b32_e32 v33, 0
	v_lshl_add_u64 v[30:31], v[20:21], 0, s[10:11]
	v_lshlrev_b64 v[26:27], 12, v[18:19]
	v_lshlrev_b64 v[20:21], 12, v[32:33]
	v_mov_b32_e32 v139, v33
	v_lshl_add_u64 v[18:19], v[134:135], 0, v[26:27]
	v_lshl_add_u64 v[20:21], v[136:137], 0, v[20:21]
	v_lshlrev_b64 v[28:29], 2, v[138:139]
	v_cndmask_b32_e32 v23, v21, v19, vcc
	v_cndmask_b32_e32 v22, v20, v18, vcc
	v_lshl_add_u64 v[18:19], v[30:31], 0, v[28:29]
	global_load_dwordx4 v[18:21], v[18:19], off
	v_lshl_add_u64 v[34:35], v[22:23], 0, v[28:29]
	global_load_dwordx4 v[22:25], v[34:35], off
	v_mov_b32_e32 v141, v33
	v_lshl_add_u64 v[26:27], s[6:7], 0, v[26:27]
	v_lshl_add_u64 v[36:37], v[26:27], 0, v[28:29]
	v_lshl_add_u64 v[26:27], v[140:141], 2, v[30:31]
	global_load_dwordx4 v[26:29], v[26:27], off
	v_or_b32_e32 v32, 0x80, v138
	s_waitcnt vmcnt(0) lgkmcnt(0)
	v_pk_mul_f32 v[16:17], v[16:17], v[20:21]
	v_pk_mul_f32 v[14:15], v[14:15], v[18:19]
	v_pk_fma_f32 v[16:17], v[16:17], 0.5, v[24:25] op_sel_hi:[1,0,1]
	v_pk_fma_f32 v[14:15], v[14:15], 0.5, v[22:23] op_sel_hi:[1,0,1]
	global_store_dwordx4 v[36:37], v[14:17], off
	global_load_dwordx4 v[14:17], v[34:35], off offset:64
	v_lshl_add_u64 v[18:19], v[32:33], 2, v[30:31]
	v_pk_mul_f32 v[12:13], v[12:13], v[28:29]
	v_pk_mul_f32 v[10:11], v[10:11], v[26:27]
	global_load_dwordx4 v[18:21], v[18:19], off
	v_or_b32_e32 v32, 0x90, v138
	s_waitcnt vmcnt(0)
	v_pk_fma_f32 v[12:13], v[12:13], 0.5, v[16:17] op_sel_hi:[1,0,1]
	v_pk_fma_f32 v[10:11], v[10:11], 0.5, v[14:15] op_sel_hi:[1,0,1]
	global_store_dwordx4 v[36:37], v[10:13], off offset:64
	global_load_dwordx4 v[10:13], v[34:35], off offset:512
	v_lshl_add_u64 v[14:15], v[32:33], 2, v[30:31]
	global_load_dwordx4 v[14:17], v[14:15], off
	s_waitcnt lgkmcnt(0)
	v_pk_mul_f32 v[8:9], v[8:9], v[20:21]
	v_pk_mul_f32 v[6:7], v[6:7], v[18:19]
	s_waitcnt vmcnt(0)
	v_pk_fma_f32 v[8:9], v[8:9], 0.5, v[12:13] op_sel_hi:[1,0,1]
	v_pk_fma_f32 v[6:7], v[6:7], 0.5, v[10:11] op_sel_hi:[1,0,1]
	global_store_dwordx4 v[36:37], v[6:9], off offset:512
	global_load_dwordx4 v[6:9], v[34:35], off offset:576
	v_pk_mul_f32 v[4:5], v[4:5], v[16:17]
	v_pk_mul_f32 v[2:3], v[2:3], v[14:15]
	s_waitcnt vmcnt(0)
	v_pk_fma_f32 v[4:5], v[4:5], 0.5, v[8:9] op_sel_hi:[1,0,1]
	v_pk_fma_f32 v[2:3], v[2:3], 0.5, v[6:7] op_sel_hi:[1,0,1]
	global_store_dwordx4 v[36:37], v[2:5], off offset:576

.LBB0_840:
	s_or_b64 exec, exec, s[6:7]
	v_mov_b32_e32 v1, v0
	v_mov_b64_e32 v[2:3], s[0:1]
	s_barrier
	global_load_dwordx2 v[2:3], v[2:3], off offset:88 sc0 sc1
	s_waitcnt vmcnt(0)
	v_readfirstlane_b32 s6, v1
	s_ashr_i32 s13, s6, 6
	s_cmp_gt_i32 s13, 7
	v_and_b32_e32 v131, 63, v1
	s_cbranch_scc1 .LBB0_843
	v_mov_b32_e32 v91, 0
	v_lshlrev_b32_e32 v90, 4, v131
	s_waitcnt lgkmcnt(0)
	v_lshl_add_u64 v[2:3], v[2:3], 0, v[90:91]
	s_movk_i32 s6, 0x1000
	v_add_co_u32_e32 v18, vcc, s6, v2
	s_lshl_b32 s6, s40, 5
	s_nop 0
	v_addc_co_u32_e32 v19, vcc, 0, v3, vcc
	global_load_dwordx4 v[2:5], v[18:19], off
	global_load_dwordx4 v[6:9], v[18:19], off offset:1024
	global_load_dwordx4 v[10:13], v[18:19], off offset:2048
	global_load_dwordx4 v[14:17], v[18:19], off offset:3072
	v_mbcnt_lo_u32_b32 v18, -1, 0
	v_mbcnt_hi_u32_b32 v18, -1, v18
	v_and_b32_e32 v19, 64, v18
	v_add_u32_e32 v19, 64, v19
	v_xor_b32_e32 v20, 1, v18
	v_cmp_lt_i32_e32 vcc, v20, v19
	s_lshl_b32 s7, s13, 2
	s_add_i32 s26, s6, 0x20a0
	v_cndmask_b32_e32 v20, v18, v20, vcc
	v_lshlrev_b32_e32 v133, 2, v20
	v_xor_b32_e32 v20, 2, v18
	v_cmp_lt_i32_e32 vcc, v20, v19
	s_add_i32 s6, s6, s7
	s_add_i32 s18, s6, 0x2080
	v_cndmask_b32_e32 v20, v18, v20, vcc
	v_lshlrev_b32_e32 v156, 2, v20
	v_xor_b32_e32 v20, 4, v18
	v_cmp_lt_i32_e32 vcc, v20, v19
	s_add_u32 s27, s38, 0x5803000
	s_addc_u32 s28, s39, 0
	v_cndmask_b32_e32 v20, v18, v20, vcc
	v_lshlrev_b32_e32 v157, 2, v20
	v_xor_b32_e32 v20, 8, v18
	v_cmp_lt_i32_e32 vcc, v20, v19
	s_ashr_i32 s19, s18, 31
	s_lshl_b64 s[6:7], s[18:19], 11
	v_cndmask_b32_e32 v20, v18, v20, vcc
	v_lshlrev_b32_e32 v158, 2, v20
	v_xor_b32_e32 v20, 16, v18
	v_cmp_lt_i32_e32 vcc, v20, v19
	v_lshl_or_b32 v92, v131, 3, s6
	v_mov_b32_e32 v93, s7
	v_cndmask_b32_e32 v20, v18, v20, vcc
	v_lshlrev_b32_e32 v159, 2, v20
	v_xor_b32_e32 v20, 32, v18
	v_cmp_lt_i32_e32 vcc, v20, v19
	s_lshl_b64 s[6:7], s[18:19], 12
	v_or_b32_e32 v94, s6, v90
	v_cndmask_b32_e32 v18, v18, v20, vcc
	v_lshlrev_b32_e32 v160, 2, v18
	v_lshlrev_b32_e32 v18, 2, v131
	v_or_b32_e32 v20, 0x100, v18
	v_or_b32_e32 v22, 0x200, v18
	v_or_b32_e32 v24, 0x300, v18
	v_mov_b32_e32 v95, s7
	v_mov_b32_e32 v161, 0x358637bd
	s_mov_b32 s19, 0xf800000
	v_mov_b32_e32 v162, 0x260
	v_lshlrev_b32_e32 v90, 2, v18
	s_movk_i32 s29, 0x7fff
	s_mov_b32 s30, 0xffff0000
	s_mov_b32 s31, 0xba00000
	v_lshlrev_b32_e32 v96, 2, v20
	v_mov_b32_e32 v97, v91
	v_lshlrev_b32_e32 v98, 2, v22
	v_mov_b32_e32 v99, v91
	v_lshlrev_b32_e32 v100, 2, v24
	v_mov_b32_e32 v101, v91
	s_mov_b32 s33, 0xba01000
	s_mov_b64 s[20:21], 0x10000
	s_mov_b64 s[22:23], 0x20000
.LBB0_842:
	v_lshl_add_u64 v[18:19], s[38:39], 0, v[94:95]
	v_lshl_add_u64 v[22:23], s[38:39], 0, v[92:93]
	v_add_co_u32_e32 v20, vcc, 0x7800000, v18
	v_add_co_u32_e64 v102, s[6:7], s31, v22
	s_nop 0
	v_addc_co_u32_e32 v21, vcc, 0, v19, vcc
	v_addc_co_u32_e64 v103, s[6:7], 0, v23, s[6:7]
	v_add_co_u32_e64 v104, s[6:7], s33, v22
	v_add_co_u32_e32 v22, vcc, 0x7801000, v18
	s_nop 0
	v_addc_co_u32_e64 v105, s[6:7], 0, v23, s[6:7]
	global_load_dwordx4 v[78:81], v[20:21], off
	global_load_dwordx4 v[74:77], v[20:21], off offset:1024
	global_load_dwordx4 v[70:73], v[20:21], off offset:2048
	global_load_dwordx4 v[66:69], v[20:21], off offset:3072
	v_addc_co_u32_e32 v23, vcc, 0, v19, vcc
	v_add_co_u32_e32 v20, vcc, 0x7802000, v18
	global_load_dwordx4 v[62:65], v[22:23], off
	global_load_dwordx4 v[58:61], v[22:23], off offset:1024
	global_load_dwordx4 v[54:57], v[22:23], off offset:2048
	global_load_dwordx4 v[50:53], v[22:23], off offset:3072
	v_addc_co_u32_e32 v21, vcc, 0, v19, vcc
	global_load_dwordx4 v[46:49], v[20:21], off
	global_load_dwordx4 v[42:45], v[20:21], off offset:1024
	global_load_dwordx4 v[38:41], v[20:21], off offset:2048
	global_load_dwordx4 v[34:37], v[20:21], off offset:3072
	v_add_co_u32_e32 v18, vcc, 0x7803000, v18
	s_ashr_i32 s8, s18, 13
	s_nop 0
	v_addc_co_u32_e32 v19, vcc, 0, v19, vcc
	global_load_dwordx4 v[30:33], v[18:19], off
	global_load_dwordx4 v[26:29], v[18:19], off offset:1024
	global_load_dwordx4 v[22:25], v[18:19], off offset:2048
	s_nop 0
	global_load_dwordx4 v[18:21], v[18:19], off offset:3072
	s_add_i32 s9, s18, 0xffffc002
	s_cmpk_lt_i32 s18, 0x4000
	s_cselect_b32 s6, s8, s9
	s_mul_hi_i32 s7, s6, 0x9000
	s_mul_i32 s6, s6, 0x9000
	s_add_u32 s6, s27, s6
	s_addc_u32 s7, s28, s7
	s_add_u32 s10, s6, 0x1000
	s_addc_u32 s11, s7, 0
	v_lshl_add_u64 v[122:123], s[6:7], 0, v[90:91]
	v_lshl_add_u64 v[86:87], s[10:11], 0, v[90:91]
	global_load_dwordx4 v[82:85], v[122:123], off
	s_add_i32 s6, s18, 0xffffc003
	global_load_dwordx4 v[86:89], v[86:87], off
	s_cmpk_lt_i32 s18, 0x3fff
	s_cselect_b32 s6, s8, s6
	s_mul_hi_i32 s7, s6, 0x9000
	s_mul_i32 s6, s6, 0x9000
	s_add_u32 s6, s27, s6
	s_addc_u32 s7, s28, s7
	v_lshl_add_u64 v[142:143], s[10:11], 0, v[96:97]
	v_lshl_add_u64 v[138:139], s[10:11], 0, v[98:99]
	v_lshl_add_u64 v[128:129], s[10:11], 0, v[100:101]
	s_add_u32 s10, s6, 0x1000
	v_lshl_add_u64 v[110:111], s[6:7], 0, v[90:91]
	s_addc_u32 s11, s7, 0
	s_add_i32 s6, s18, 0xffffc004
	s_cmpk_lt_i32 s18, 0x3ffe
	s_cselect_b32 s6, s8, s6
	s_mul_hi_i32 s7, s6, 0x9000
	s_mul_i32 s6, s6, 0x9000
	v_lshl_add_u64 v[124:125], s[10:11], 0, v[90:91]
	v_lshl_add_u64 v[118:119], s[10:11], 0, v[96:97]
	v_lshl_add_u64 v[114:115], s[10:11], 0, v[98:99]
	v_lshl_add_u64 v[112:113], s[10:11], 0, v[100:101]
	s_add_u32 s10, s27, s6
	s_addc_u32 s11, s28, s7
	s_add_u32 s6, s10, 0x1000
	s_addc_u32 s7, s11, 0
	s_add_i32 s9, s18, 0xffffc005
	s_cmpk_lt_i32 s18, 0x3ffd
	v_lshl_add_u64 v[146:147], s[6:7], 0, v[90:91]
	v_lshl_add_u64 v[144:145], s[6:7], 0, v[96:97]
	v_lshl_add_u64 v[140:141], s[6:7], 0, v[98:99]
	v_lshl_add_u64 v[126:127], s[6:7], 0, v[100:101]
	s_cselect_b32 s6, s8, s9
	s_mul_hi_i32 s7, s6, 0x9000
	s_mul_i32 s6, s6, 0x9000
	s_add_u32 s6, s27, s6
	s_addc_u32 s7, s28, s7
	s_add_u32 s24, s6, 0x1000
	v_lshl_add_u64 v[106:107], s[6:7], 0, v[90:91]
	s_addc_u32 s25, s7, 0
	v_lshl_add_u64 v[108:109], s[10:11], 0, v[90:91]
	v_lshl_add_u64 v[120:121], s[24:25], 0, v[90:91]
	v_lshl_add_u64 v[116:117], s[24:25], 0, v[96:97]
	s_add_i32 s18, s18, 32
	v_lshl_add_u64 v[92:93], v[92:93], 0, s[20:21]
	v_lshl_add_u64 v[94:95], v[94:95], 0, s[22:23]
	s_cmp_lt_i32 s18, s26
	s_waitcnt vmcnt(0) lgkmcnt(0)
	v_pk_mul_f32 v[148:149], v[80:81], v[80:81]
	v_pk_mul_f32 v[150:151], v[78:79], v[78:79]
	v_pk_mul_f32 v[152:153], v[76:77], v[76:77]
	v_pk_mul_f32 v[154:155], v[74:75], v[74:75]
	v_mul_f32_e32 v164, v71, v71
	v_mul_f32_e32 v166, v73, v73
	v_pk_mov_b32 v[168:169], v[150:151], v[148:149] op_sel:[1,0]
	v_mov_b32_e32 v151, v149
	v_pk_mov_b32 v[148:149], v[154:155], v[152:153] op_sel:[1,0]
	v_mov_b32_e32 v155, v153
	v_mul_f32_e32 v177, v68, v68
	v_mul_f32_e32 v179, v69, v69
	v_pk_fma_f32 v[152:153], v[70:71], v[70:71], v[164:165] op_sel_hi:[1,1,0]
	v_pk_fma_f32 v[164:165], v[72:73], v[72:73], v[166:167] op_sel_hi:[1,1,0]
	v_pk_mul_f32 v[166:167], v[64:65], v[64:65]
	v_pk_mul_f32 v[170:171], v[62:63], v[62:63]
	v_pk_mul_f32 v[172:173], v[60:61], v[60:61]
	v_pk_mul_f32 v[174:175], v[58:59], v[58:59]
	v_mul_f32_e32 v176, v55, v55
	v_mul_f32_e32 v178, v57, v57
	v_pk_add_f32 v[150:151], v[168:169], v[150:151]
	v_pk_add_f32 v[148:149], v[148:149], v[154:155]
	v_mul_f32_e32 v163, v66, v66
	v_mul_f32_e32 v187, v67, v67
	v_mov_b32_e32 v153, v177
	v_mov_b32_e32 v165, v179
	v_pk_mov_b32 v[154:155], v[170:171], v[166:167] op_sel:[1,0]
	v_mov_b32_e32 v171, v167
	v_pk_mov_b32 v[166:167], v[174:175], v[172:173] op_sel:[1,0]
	v_mov_b32_e32 v175, v173
	v_pk_fma_f32 v[168:169], v[54:55], v[54:55], v[176:177] op_sel_hi:[1,1,0]
	v_pk_fma_f32 v[172:173], v[56:57], v[56:57], v[178:179] op_sel_hi:[1,1,0]
	v_pk_mul_f32 v[176:177], v[48:49], v[48:49]
	v_pk_mul_f32 v[178:179], v[46:47], v[46:47]
	v_pk_add_f32 v[188:189], v[150:151], v[150:151] op_sel:[0,1] op_sel_hi:[1,0]
	v_pk_add_f32 v[190:191], v[148:149], v[148:149] op_sel:[0,1] op_sel_hi:[1,0]
	v_mul_f32_e32 v185, v52, v52
	v_pk_mul_f32 v[180:181], v[44:45], v[44:45]
	v_pk_mul_f32 v[182:183], v[42:43], v[42:43]
	v_mul_f32_e32 v184, v39, v39
	v_mul_f32_e32 v186, v41, v41
	v_pk_add_f32 v[164:165], v[152:153], v[164:165]
	v_pk_add_f32 v[148:149], v[154:155], v[170:171]
	v_pk_add_f32 v[150:151], v[166:167], v[174:175]
	v_pk_mov_b32 v[152:153], v[178:179], v[176:177] op_sel:[1,0]
	v_mov_b32_e32 v179, v177
	v_mov_b32_e32 v189, v163
	v_mov_b32_e32 v191, v187
	v_mul_f32_e32 v193, v50, v50
	v_mul_f32_e32 v198, v51, v51
	v_mul_f32_e32 v192, v53, v53
	v_mul_f32_e32 v201, v36, v36
	v_mul_f32_e32 v202, v37, v37
	v_pk_mov_b32 v[154:155], v[182:183], v[180:181] op_sel:[1,0]
	v_mov_b32_e32 v183, v181
	v_pk_fma_f32 v[166:167], v[38:39], v[38:39], v[184:185] op_sel_hi:[1,1,0]
	v_pk_fma_f32 v[170:171], v[40:41], v[40:41], v[186:187] op_sel_hi:[1,1,0]
	v_pk_add_f32 v[194:195], v[148:149], v[148:149] op_sel:[0,1] op_sel_hi:[1,0]
	v_pk_add_f32 v[196:197], v[150:151], v[150:151] op_sel:[0,1] op_sel_hi:[1,0]
	v_pk_add_f32 v[152:153], v[152:153], v[178:179]
	v_pk_add_f32 v[178:179], v[188:189], v[190:191]
	v_mov_b32_e32 v169, v185
	v_mov_b32_e32 v173, v192
	v_pk_mul_f32 v[174:175], v[32:33], v[32:33]
	v_pk_mul_f32 v[176:177], v[30:31], v[30:31]
	v_pk_mul_f32 v[180:181], v[28:29], v[28:29]
	v_pk_mul_f32 v[184:185], v[26:27], v[26:27]
	v_pk_add_f32 v[154:155], v[154:155], v[182:183]
	v_mov_b32_e32 v167, v201
	v_mov_b32_e32 v171, v202
	v_mov_b32_e32 v195, v193
	v_mov_b32_e32 v197, v198
	v_pk_add_f32 v[164:165], v[178:179], v[164:165]
	v_mul_f32_e32 v199, v34, v34
	v_mul_f32_e32 v200, v35, v35
	v_pk_add_f32 v[168:169], v[168:169], v[172:173]
	v_pk_mov_b32 v[172:173], v[176:177], v[174:175] op_sel:[1,0]
	v_mov_b32_e32 v177, v175
	v_pk_mov_b32 v[174:175], v[184:185], v[180:181] op_sel:[1,0]
	v_mov_b32_e32 v185, v181
	v_pk_add_f32 v[180:181], v[152:153], v[152:153] op_sel:[0,1] op_sel_hi:[1,0]
	v_pk_add_f32 v[182:183], v[154:155], v[154:155] op_sel:[0,1] op_sel_hi:[1,0]
	v_pk_add_f32 v[166:167], v[166:167], v[170:171]
	v_pk_add_f32 v[170:171], v[194:195], v[196:197]
	v_add_f32_e32 v163, v164, v165
	v_mov_b32_e32 v181, v199
	v_mov_b32_e32 v183, v200
	v_pk_add_f32 v[164:165], v[170:171], v[168:169]
	ds_bpermute_b32 v171, v133, v163
	v_pk_add_f32 v[168:169], v[180:181], v[182:183]
	v_add_f32_e32 v170, v164, v165
	v_pk_add_f32 v[164:165], v[168:169], v[166:167]
	ds_bpermute_b32 v166, v133, v170
	v_add_f32_e32 v164, v164, v165
	ds_bpermute_b32 v165, v133, v164
	s_waitcnt lgkmcnt(2)
	v_add_f32_e32 v163, v163, v171
	ds_bpermute_b32 v167, v156, v163
	s_waitcnt lgkmcnt(2)
	v_add_f32_e32 v166, v170, v166
	ds_bpermute_b32 v168, v156, v166
	s_waitcnt lgkmcnt(2)
	v_add_f32_e32 v164, v164, v165
	ds_bpermute_b32 v165, v156, v164
	s_waitcnt lgkmcnt(2)
	v_add_f32_e32 v163, v163, v167
	ds_bpermute_b32 v167, v157, v163
	s_waitcnt lgkmcnt(2)
	v_add_f32_e32 v166, v166, v168
	ds_bpermute_b32 v168, v157, v166
	s_waitcnt lgkmcnt(2)
	v_add_f32_e32 v164, v164, v165
	ds_bpermute_b32 v165, v157, v164
	s_waitcnt lgkmcnt(2)
	v_add_f32_e32 v163, v163, v167
	ds_bpermute_b32 v167, v158, v163
	s_waitcnt lgkmcnt(2)
	v_add_f32_e32 v166, v166, v168
	ds_bpermute_b32 v168, v158, v166
	s_waitcnt lgkmcnt(2)
	v_add_f32_e32 v164, v164, v165
	ds_bpermute_b32 v165, v158, v164
	s_waitcnt lgkmcnt(2)
	v_add_f32_e32 v163, v163, v167
	ds_bpermute_b32 v167, v159, v163
	s_waitcnt lgkmcnt(2)
	v_add_f32_e32 v166, v166, v168
	ds_bpermute_b32 v168, v159, v166
	s_waitcnt lgkmcnt(2)
	v_add_f32_e32 v164, v164, v165
	ds_bpermute_b32 v165, v159, v164
	s_waitcnt lgkmcnt(2)
	v_add_f32_e32 v163, v163, v167
	ds_bpermute_b32 v167, v160, v163
	s_waitcnt lgkmcnt(2)
	v_add_f32_e32 v166, v166, v168
	ds_bpermute_b32 v168, v160, v166
	s_waitcnt lgkmcnt(2)
	v_add_f32_e32 v164, v164, v165
	ds_bpermute_b32 v165, v160, v164
	s_waitcnt lgkmcnt(2)
	v_add_f32_e32 v163, v163, v167
	v_fmamk_f32 v163, v163, 0x3a800000, v161
	s_waitcnt lgkmcnt(1)
	v_add_f32_e32 v166, v166, v168
	v_mul_f32_e32 v167, 0x4f800000, v163
	v_cmp_gt_f32_e32 vcc, s19, v163
	v_fmamk_f32 v166, v166, 0x3a800000, v161
	s_waitcnt lgkmcnt(0)
	v_add_f32_e32 v164, v164, v165
	v_cndmask_b32_e32 v163, v163, v167, vcc
	v_mul_f32_e32 v165, 0x4f800000, v166
	v_cmp_gt_f32_e64 s[6:7], s19, v166
	v_sqrt_f32_e32 v167, v163
	v_fmamk_f32 v164, v164, 0x3a800000, v161
	v_cndmask_b32_e64 v165, v166, v165, s[6:7]
	v_mul_f32_e32 v166, 0x4f800000, v164
	v_cmp_gt_f32_e64 s[8:9], s19, v164
	v_sqrt_f32_e32 v168, v165
	v_add_u32_e32 v169, -1, v167
	v_cndmask_b32_e64 v164, v164, v166, s[8:9]
	v_sqrt_f32_e32 v166, v164
	v_add_u32_e32 v170, 1, v167
	v_fma_f32 v171, -v169, v167, v163
	v_pk_add_f32 v[152:153], v[172:173], v[176:177]
	v_fma_f32 v172, -v170, v167, v163
	v_add_u32_e32 v173, -1, v168
	v_cmp_ge_f32_e64 s[10:11], 0, v171
	v_pk_add_f32 v[154:155], v[174:175], v[184:185]
	v_add_u32_e32 v174, 1, v168
	v_cndmask_b32_e64 v167, v167, v169, s[10:11]
	v_fma_f32 v169, -v173, v168, v165
	v_cmp_lt_f32_e64 s[10:11], 0, v172
	v_fma_f32 v171, -v174, v168, v165
	v_add_u32_e32 v175, -1, v166
	v_cndmask_b32_e64 v167, v167, v170, s[10:11]
	v_cmp_ge_f32_e64 s[10:11], 0, v169
	v_add_u32_e32 v176, 1, v166
	v_fma_f32 v169, -v175, v166, v164
	v_cndmask_b32_e64 v168, v168, v173, s[10:11]
	v_cmp_lt_f32_e64 s[10:11], 0, v171
	v_fma_f32 v170, -v176, v166, v164
	v_mul_f32_e32 v171, 0x37800000, v167
	v_cndmask_b32_e64 v168, v168, v174, s[10:11]
	v_cmp_ge_f32_e64 s[10:11], 0, v169
	v_cndmask_b32_e32 v167, v167, v171, vcc
	v_cmp_class_f32_e32 vcc, v163, v162
	v_cndmask_b32_e64 v166, v166, v175, s[10:11]
	v_cmp_lt_f32_e64 s[10:11], 0, v170
	v_mul_f32_e32 v169, 0x37800000, v168
	v_cndmask_b32_e32 v163, v167, v163, vcc
	v_cndmask_b32_e64 v166, v166, v176, s[10:11]
	v_cndmask_b32_e64 v167, v168, v169, s[6:7]
	v_cmp_class_f32_e32 vcc, v165, v162
	v_mul_f32_e32 v168, 0x37800000, v166
	v_div_scale_f32 v169, s[6:7], v163, v163, 1.0
	v_cndmask_b32_e32 v165, v167, v165, vcc
	v_cndmask_b32_e64 v166, v166, v168, s[8:9]
	v_cmp_class_f32_e32 vcc, v164, v162
	v_rcp_f32_e32 v167, v169
	v_div_scale_f32 v168, s[8:9], v165, v165, 1.0
	v_cndmask_b32_e32 v166, v166, v164, vcc
	v_rcp_f32_e32 v172, v168
	v_div_scale_f32 v173, s[10:11], v166, v166, 1.0
	v_rcp_f32_e32 v175, v173
	v_fma_f32 v164, -v169, v167, 1.0
	v_div_scale_f32 v170, s[6:7], 1.0, v163, 1.0
	v_fmac_f32_e32 v167, v164, v167
	v_fma_f32 v164, -v168, v172, 1.0
	v_mul_f32_e32 v176, v170, v167
	v_div_scale_f32 v171, s[8:9], 1.0, v165, 1.0
	v_fmac_f32_e32 v172, v164, v172
	v_fma_f32 v164, -v173, v175, 1.0
	v_fma_f32 v177, -v169, v176, v170
	v_div_scale_f32 v174, s[10:11], 1.0, v166, 1.0
	v_mul_f32_e32 v178, v171, v172
	v_fmac_f32_e32 v175, v164, v175
	v_fmac_f32_e32 v176, v177, v167
	v_fma_f32 v164, -v168, v178, v171
	v_mul_f32_e32 v177, v174, v175
	v_fma_f32 v169, -v169, v176, v170
	s_mov_b64 vcc, s[6:7]
	v_fmac_f32_e32 v178, v164, v172
	v_fma_f32 v164, -v173, v177, v174
	v_div_fmas_f32 v167, v169, v167, v176
	v_fma_f32 v168, -v168, v178, v171
	v_fmac_f32_e32 v177, v164, v175
	v_div_fixup_f32 v164, v167, v163, 1.0
	s_mov_b64 vcc, s[8:9]
	v_div_fmas_f32 v163, v168, v172, v178
	v_fma_f32 v167, -v173, v177, v174
	v_pk_mul_f32 v[80:81], v[80:81], v[164:165] op_sel_hi:[1,0]
	v_pk_mul_f32 v[78:79], v[78:79], v[164:165] op_sel_hi:[1,0]
	s_mov_b64 vcc, s[10:11]
	v_pk_add_f32 v[88:89], v[88:89], 1.0 op_sel_hi:[1,0]
	v_pk_add_f32 v[86:87], v[86:87], 1.0 op_sel_hi:[1,0]
	v_pk_mul_f32 v[76:77], v[76:77], v[164:165] op_sel_hi:[1,0]
	v_pk_mul_f32 v[74:75], v[74:75], v[164:165] op_sel_hi:[1,0]
	v_pk_mul_f32 v[72:73], v[72:73], v[164:165] op_sel_hi:[1,0]
	v_pk_mul_f32 v[70:71], v[70:71], v[164:165] op_sel_hi:[1,0]
	v_pk_mul_f32 v[68:69], v[68:69], v[164:165] op_sel_hi:[1,0]
	v_pk_mul_f32 v[66:67], v[66:67], v[164:165] op_sel_hi:[1,0]
	v_div_fixup_f32 v164, v163, v165, 1.0
	v_div_fmas_f32 v163, v167, v175, v177
	v_pk_mul_f32 v[78:79], v[78:79], v[2:3]
	v_pk_mul_f32 v[80:81], v[80:81], v[4:5]
	v_pk_mul_f32 v[64:65], v[64:65], v[164:165] op_sel_hi:[1,0]
	v_pk_mul_f32 v[62:63], v[62:63], v[164:165] op_sel_hi:[1,0]
	v_pk_mul_f32 v[60:61], v[60:61], v[164:165] op_sel_hi:[1,0]
	v_pk_mul_f32 v[58:59], v[58:59], v[164:165] op_sel_hi:[1,0]
	v_pk_mul_f32 v[56:57], v[56:57], v[164:165] op_sel_hi:[1,0]
	v_pk_mul_f32 v[54:55], v[54:55], v[164:165] op_sel_hi:[1,0]
	v_pk_mul_f32 v[52:53], v[52:53], v[164:165] op_sel_hi:[1,0]
	v_pk_mul_f32 v[50:51], v[50:51], v[164:165] op_sel_hi:[1,0]
	v_div_fixup_f32 v164, v163, v166, 1.0
	v_pk_fma_f32 v[80:81], v[80:81], v[88:89], v[84:85]
	v_pk_fma_f32 v[78:79], v[78:79], v[86:87], v[82:83]
	v_pk_mul_f32 v[82:83], v[50:51], v[14:15]
	v_pk_mul_f32 v[84:85], v[52:53], v[16:17]
	v_pk_mul_f32 v[48:49], v[48:49], v[164:165] op_sel_hi:[1,0]
	v_pk_mul_f32 v[46:47], v[46:47], v[164:165] op_sel_hi:[1,0]
	v_bfe_u32 v50, v78, 16, 1
	v_bfe_u32 v52, v80, 16, 1
	v_bfe_u32 v51, v79, 16, 1
	v_bfe_u32 v53, v81, 16, 1
	v_pk_mul_f32 v[86:87], v[46:47], v[2:3]
	v_pk_mul_f32 v[88:89], v[48:49], v[4:5]
	v_add3_u32 v46, v78, v50, s29
	v_add3_u32 v48, v80, v52, s29
	v_add3_u32 v47, v79, v51, s29
	v_add3_u32 v49, v81, v53, s29
	v_lshrrev_b32_e32 v46, 16, v46
	v_lshrrev_b32_e32 v48, 16, v48
	v_and_or_b32 v46, v47, s30, v46
	v_and_or_b32 v47, v49, s30, v48
	global_store_dwordx2 v[102:103], v[46:47], off
	global_load_dwordx4 v[46:49], v[142:143], off
	s_nop 0
	global_load_dwordx4 v[50:53], v[122:123], off offset:1024
	v_pk_mul_f32 v[74:75], v[74:75], v[6:7]
	v_pk_mul_f32 v[76:77], v[76:77], v[8:9]
	v_pk_mul_f32 v[70:71], v[70:71], v[10:11]
	v_pk_mul_f32 v[72:73], v[72:73], v[12:13]
	v_pk_mul_f32 v[66:67], v[66:67], v[14:15]
	v_pk_mul_f32 v[68:69], v[68:69], v[16:17]
	v_pk_mul_f32 v[62:63], v[62:63], v[2:3]
	v_pk_mul_f32 v[64:65], v[64:65], v[4:5]
	v_pk_mul_f32 v[58:59], v[58:59], v[6:7]
	v_pk_mul_f32 v[60:61], v[60:61], v[8:9]
	v_pk_mul_f32 v[54:55], v[54:55], v[10:11]
	v_pk_mul_f32 v[56:57], v[56:57], v[12:13]
	v_pk_mul_f32 v[44:45], v[44:45], v[164:165] op_sel_hi:[1,0]
	v_pk_mul_f32 v[42:43], v[42:43], v[164:165] op_sel_hi:[1,0]
	v_pk_mul_f32 v[44:45], v[44:45], v[8:9]
	v_pk_mul_f32 v[42:43], v[42:43], v[6:7]
	v_pk_mul_f32 v[40:41], v[40:41], v[164:165] op_sel_hi:[1,0]
	v_pk_mul_f32 v[38:39], v[38:39], v[164:165] op_sel_hi:[1,0]
	v_pk_mul_f32 v[40:41], v[40:41], v[12:13]
	v_pk_mul_f32 v[38:39], v[38:39], v[10:11]
	v_pk_mul_f32 v[36:37], v[36:37], v[164:165] op_sel_hi:[1,0]
	v_pk_mul_f32 v[34:35], v[34:35], v[164:165] op_sel_hi:[1,0]
	v_pk_mul_f32 v[36:37], v[36:37], v[16:17]
	v_pk_mul_f32 v[34:35], v[34:35], v[14:15]
	v_mul_f32_e32 v186, v23, v23
	v_mul_f32_e32 v192, v25, v25
	v_mul_f32_e32 v203, v18, v18
	v_mul_f32_e32 v204, v19, v19
	v_mul_f32_e32 v205, v20, v20
	v_mul_f32_e32 v206, v21, v21
	v_pk_fma_f32 v[148:149], v[22:23], v[22:23], v[186:187] op_sel_hi:[1,1,0]
	v_pk_fma_f32 v[150:151], v[24:25], v[24:25], v[192:193] op_sel_hi:[1,1,0]
	v_mov_b32_e32 v149, v205
	v_mov_b32_e32 v151, v206
	s_waitcnt vmcnt(0) lgkmcnt(0)
	v_pk_add_f32 v[48:49], v[48:49], 1.0 op_sel_hi:[1,0]
	v_pk_add_f32 v[46:47], v[46:47], 1.0 op_sel_hi:[1,0]
	v_pk_fma_f32 v[48:49], v[76:77], v[48:49], v[52:53]
	v_pk_fma_f32 v[46:47], v[74:75], v[46:47], v[50:51]
	v_bfe_u32 v52, v48, 16, 1
	v_bfe_u32 v50, v46, 16, 1
	v_bfe_u32 v51, v47, 16, 1
	v_bfe_u32 v53, v49, 16, 1
	v_add3_u32 v46, v46, v50, s29
	v_add3_u32 v48, v48, v52, s29
	v_add3_u32 v47, v47, v51, s29
	v_add3_u32 v49, v49, v53, s29
	v_lshrrev_b32_e32 v46, 16, v46
	v_lshrrev_b32_e32 v48, 16, v48
	v_and_or_b32 v46, v47, s30, v46
	v_and_or_b32 v47, v49, s30, v48
	global_store_dwordx2 v[102:103], v[46:47], off offset:512
	global_load_dwordx4 v[46:49], v[138:139], off
	s_nop 0
	global_load_dwordx4 v[50:53], v[122:123], off offset:2048
	s_waitcnt vmcnt(0) lgkmcnt(0)
	v_pk_add_f32 v[48:49], v[48:49], 1.0 op_sel_hi:[1,0]
	v_pk_add_f32 v[46:47], v[46:47], 1.0 op_sel_hi:[1,0]
	v_pk_fma_f32 v[48:49], v[72:73], v[48:49], v[52:53]
	v_pk_fma_f32 v[46:47], v[70:71], v[46:47], v[50:51]
	v_bfe_u32 v52, v48, 16, 1
	v_bfe_u32 v50, v46, 16, 1
	v_bfe_u32 v51, v47, 16, 1
	v_bfe_u32 v53, v49, 16, 1
	v_add3_u32 v46, v46, v50, s29
	v_add3_u32 v48, v48, v52, s29
	v_add3_u32 v47, v47, v51, s29
	v_add3_u32 v49, v49, v53, s29
	v_lshrrev_b32_e32 v46, 16, v46
	v_lshrrev_b32_e32 v48, 16, v48
	v_and_or_b32 v46, v47, s30, v46
	v_and_or_b32 v47, v49, s30, v48
	global_store_dwordx2 v[102:103], v[46:47], off offset:1024
	global_load_dwordx4 v[46:49], v[128:129], off
	s_nop 0
	global_load_dwordx4 v[50:53], v[122:123], off offset:3072
	s_waitcnt vmcnt(0) lgkmcnt(0)
	v_pk_add_f32 v[48:49], v[48:49], 1.0 op_sel_hi:[1,0]
	v_pk_add_f32 v[46:47], v[46:47], 1.0 op_sel_hi:[1,0]
	v_pk_fma_f32 v[48:49], v[68:69], v[48:49], v[52:53]
	v_pk_fma_f32 v[46:47], v[66:67], v[46:47], v[50:51]
	v_bfe_u32 v52, v48, 16, 1
	v_bfe_u32 v50, v46, 16, 1
	v_bfe_u32 v51, v47, 16, 1
	v_bfe_u32 v53, v49, 16, 1
	v_add3_u32 v46, v46, v50, s29
	v_add3_u32 v48, v48, v52, s29
	v_add3_u32 v47, v47, v51, s29
	v_add3_u32 v49, v49, v53, s29
	v_lshrrev_b32_e32 v46, 16, v46
	v_lshrrev_b32_e32 v48, 16, v48
	v_and_or_b32 v46, v47, s30, v46
	v_and_or_b32 v47, v49, s30, v48
	global_store_dwordx2 v[102:103], v[46:47], off offset:1536
	global_load_dwordx4 v[46:49], v[124:125], off
	s_nop 0
	global_load_dwordx4 v[50:53], v[110:111], off
	s_waitcnt vmcnt(0) lgkmcnt(0)
	v_pk_add_f32 v[48:49], v[48:49], 1.0 op_sel_hi:[1,0]
	v_pk_add_f32 v[46:47], v[46:47], 1.0 op_sel_hi:[1,0]
	v_pk_fma_f32 v[48:49], v[64:65], v[48:49], v[52:53]
	v_pk_fma_f32 v[46:47], v[62:63], v[46:47], v[50:51]
	v_bfe_u32 v52, v48, 16, 1
	v_bfe_u32 v50, v46, 16, 1
	v_bfe_u32 v51, v47, 16, 1
	v_bfe_u32 v53, v49, 16, 1
	v_add3_u32 v46, v46, v50, s29
	v_add3_u32 v48, v48, v52, s29
	v_add3_u32 v47, v47, v51, s29
	v_add3_u32 v49, v49, v53, s29
	v_lshrrev_b32_e32 v46, 16, v46
	v_lshrrev_b32_e32 v48, 16, v48
	v_and_or_b32 v46, v47, s30, v46
	v_and_or_b32 v47, v49, s30, v48
	global_store_dwordx2 v[102:103], v[46:47], off offset:2048
	global_load_dwordx4 v[46:49], v[118:119], off
	s_nop 0
	global_load_dwordx4 v[50:53], v[110:111], off offset:1024
	s_waitcnt vmcnt(0) lgkmcnt(0)
	v_pk_add_f32 v[48:49], v[48:49], 1.0 op_sel_hi:[1,0]
	v_pk_add_f32 v[46:47], v[46:47], 1.0 op_sel_hi:[1,0]
	v_pk_fma_f32 v[48:49], v[60:61], v[48:49], v[52:53]
	v_pk_fma_f32 v[46:47], v[58:59], v[46:47], v[50:51]
	v_bfe_u32 v52, v48, 16, 1
	v_bfe_u32 v50, v46, 16, 1
	v_bfe_u32 v51, v47, 16, 1
	v_bfe_u32 v53, v49, 16, 1
	v_add3_u32 v46, v46, v50, s29
	v_add3_u32 v48, v48, v52, s29
	v_add3_u32 v47, v47, v51, s29
	v_add3_u32 v49, v49, v53, s29
	v_lshrrev_b32_e32 v46, 16, v46
	v_lshrrev_b32_e32 v48, 16, v48
	v_and_or_b32 v46, v47, s30, v46
	v_and_or_b32 v47, v49, s30, v48
	global_store_dwordx2 v[102:103], v[46:47], off offset:2560
	global_load_dwordx4 v[46:49], v[114:115], off
	s_nop 0
	global_load_dwordx4 v[50:53], v[110:111], off offset:2048
	v_pk_add_f32 v[58:59], v[148:149], v[150:151]
	s_waitcnt vmcnt(0) lgkmcnt(0)
	v_pk_add_f32 v[48:49], v[48:49], 1.0 op_sel_hi:[1,0]
	v_pk_add_f32 v[46:47], v[46:47], 1.0 op_sel_hi:[1,0]
	v_pk_fma_f32 v[48:49], v[56:57], v[48:49], v[52:53]
	v_pk_fma_f32 v[46:47], v[54:55], v[46:47], v[50:51]
	v_bfe_u32 v52, v48, 16, 1
	v_bfe_u32 v50, v46, 16, 1
	v_bfe_u32 v51, v47, 16, 1
	v_bfe_u32 v53, v49, 16, 1
	v_add3_u32 v46, v46, v50, s29
	v_add3_u32 v48, v48, v52, s29
	v_add3_u32 v47, v47, v51, s29
	v_add3_u32 v49, v49, v53, s29
	v_lshrrev_b32_e32 v46, 16, v46
	v_lshrrev_b32_e32 v48, 16, v48
	v_and_or_b32 v46, v47, s30, v46
	v_and_or_b32 v47, v49, s30, v48
	global_store_dwordx2 v[102:103], v[46:47], off offset:3072
	global_load_dwordx4 v[46:49], v[112:113], off
	s_nop 0
	global_load_dwordx4 v[50:53], v[110:111], off offset:3072
	v_pk_add_f32 v[54:55], v[152:153], v[152:153] op_sel:[0,1] op_sel_hi:[1,0]
	v_pk_add_f32 v[56:57], v[154:155], v[154:155] op_sel:[0,1] op_sel_hi:[1,0]
	v_mov_b32_e32 v55, v203
	v_mov_b32_e32 v57, v204
	s_waitcnt vmcnt(0) lgkmcnt(0)
	v_pk_add_f32 v[48:49], v[48:49], 1.0 op_sel_hi:[1,0]
	v_pk_add_f32 v[46:47], v[46:47], 1.0 op_sel_hi:[1,0]
	v_pk_fma_f32 v[48:49], v[84:85], v[48:49], v[52:53]
	v_pk_fma_f32 v[46:47], v[82:83], v[46:47], v[50:51]
	v_bfe_u32 v52, v48, 16, 1
	v_bfe_u32 v50, v46, 16, 1
	v_bfe_u32 v51, v47, 16, 1
	v_bfe_u32 v53, v49, 16, 1
	v_add3_u32 v46, v46, v50, s29
	v_add3_u32 v48, v48, v52, s29
	v_add3_u32 v47, v47, v51, s29
	v_add3_u32 v49, v49, v53, s29
	v_lshrrev_b32_e32 v46, 16, v46
	v_lshrrev_b32_e32 v48, 16, v48
	v_and_or_b32 v46, v47, s30, v46
	v_and_or_b32 v47, v49, s30, v48
	global_store_dwordx2 v[102:103], v[46:47], off offset:3584
	global_load_dwordx4 v[46:49], v[146:147], off
	s_nop 0
	global_load_dwordx4 v[50:53], v[108:109], off
	s_waitcnt vmcnt(0) lgkmcnt(0)
	v_pk_add_f32 v[48:49], v[48:49], 1.0 op_sel_hi:[1,0]
	v_pk_add_f32 v[46:47], v[46:47], 1.0 op_sel_hi:[1,0]
	v_pk_fma_f32 v[48:49], v[88:89], v[48:49], v[52:53]
	v_pk_fma_f32 v[46:47], v[86:87], v[46:47], v[50:51]
	v_bfe_u32 v52, v48, 16, 1
	v_bfe_u32 v50, v46, 16, 1
	v_bfe_u32 v51, v47, 16, 1
	v_bfe_u32 v53, v49, 16, 1
	v_add3_u32 v46, v46, v50, s29
	v_add3_u32 v48, v48, v52, s29
	v_add3_u32 v47, v47, v51, s29
	v_add3_u32 v49, v49, v53, s29
	v_lshrrev_b32_e32 v46, 16, v46
	v_lshrrev_b32_e32 v48, 16, v48
	v_and_or_b32 v46, v47, s30, v46
	v_and_or_b32 v47, v49, s30, v48
	global_store_dwordx2 v[104:105], v[46:47], off
	global_load_dwordx4 v[46:49], v[144:145], off
	s_nop 0
	global_load_dwordx4 v[50:53], v[108:109], off offset:1024
	s_waitcnt vmcnt(0) lgkmcnt(0)
	v_pk_add_f32 v[48:49], v[48:49], 1.0 op_sel_hi:[1,0]
	v_pk_add_f32 v[46:47], v[46:47], 1.0 op_sel_hi:[1,0]
	v_pk_fma_f32 v[44:45], v[44:45], v[48:49], v[52:53]
	v_pk_fma_f32 v[42:43], v[42:43], v[46:47], v[50:51]
	v_bfe_u32 v48, v44, 16, 1
	v_bfe_u32 v46, v42, 16, 1
	v_bfe_u32 v47, v43, 16, 1
	v_bfe_u32 v49, v45, 16, 1
	v_add3_u32 v42, v42, v46, s29
	v_add3_u32 v44, v44, v48, s29
	v_add3_u32 v43, v43, v47, s29
	v_add3_u32 v45, v45, v49, s29
	v_lshrrev_b32_e32 v42, 16, v42
	v_lshrrev_b32_e32 v44, 16, v44
	v_and_or_b32 v42, v43, s30, v42
	v_and_or_b32 v43, v45, s30, v44
	global_store_dwordx2 v[104:105], v[42:43], off offset:512
	global_load_dwordx4 v[42:45], v[140:141], off
	s_nop 0
	global_load_dwordx4 v[46:49], v[108:109], off offset:2048
	v_pk_add_f32 v[50:51], v[54:55], v[56:57]
	s_waitcnt vmcnt(0) lgkmcnt(0)
	v_pk_add_f32 v[44:45], v[44:45], 1.0 op_sel_hi:[1,0]
	v_pk_add_f32 v[42:43], v[42:43], 1.0 op_sel_hi:[1,0]
	v_pk_fma_f32 v[40:41], v[40:41], v[44:45], v[48:49]
	v_pk_fma_f32 v[38:39], v[38:39], v[42:43], v[46:47]
	v_bfe_u32 v44, v40, 16, 1
	v_bfe_u32 v42, v38, 16, 1
	v_bfe_u32 v43, v39, 16, 1
	v_bfe_u32 v45, v41, 16, 1
	v_add3_u32 v38, v38, v42, s29
	v_add3_u32 v40, v40, v44, s29
	v_add3_u32 v39, v39, v43, s29
	v_add3_u32 v41, v41, v45, s29
	v_lshrrev_b32_e32 v38, 16, v38
	v_lshrrev_b32_e32 v40, 16, v40
	v_and_or_b32 v38, v39, s30, v38
	v_and_or_b32 v39, v41, s30, v40
	global_store_dwordx2 v[104:105], v[38:39], off offset:1024
	global_load_dwordx4 v[38:41], v[126:127], off
	s_nop 0
	global_load_dwordx4 v[42:45], v[108:109], off offset:3072
	v_pk_add_f32 v[50:51], v[50:51], v[58:59]
	s_waitcnt vmcnt(0) lgkmcnt(0)
	v_pk_add_f32 v[40:41], v[40:41], 1.0 op_sel_hi:[1,0]
	v_pk_add_f32 v[38:39], v[38:39], 1.0 op_sel_hi:[1,0]
	v_pk_fma_f32 v[36:37], v[36:37], v[40:41], v[44:45]
	v_pk_fma_f32 v[34:35], v[34:35], v[38:39], v[42:43]
	v_bfe_u32 v40, v36, 16, 1
	v_bfe_u32 v38, v34, 16, 1
	v_bfe_u32 v39, v35, 16, 1
	v_bfe_u32 v41, v37, 16, 1
	v_add3_u32 v34, v34, v38, s29
	v_add3_u32 v36, v36, v40, s29
	v_add3_u32 v35, v35, v39, s29
	v_add3_u32 v37, v37, v41, s29
	v_lshrrev_b32_e32 v34, 16, v34
	v_lshrrev_b32_e32 v36, 16, v36
	v_and_or_b32 v34, v35, s30, v34
	v_and_or_b32 v35, v37, s30, v36
	global_store_dwordx2 v[104:105], v[34:35], off offset:1536
	global_load_dwordx4 v[34:37], v[120:121], off
	s_nop 0
	global_load_dwordx4 v[38:41], v[106:107], off
	v_add_f32_e32 v50, v50, v51
	ds_bpermute_b32 v51, v133, v50
	s_waitcnt lgkmcnt(0)
	v_add_f32_e32 v50, v50, v51
	ds_bpermute_b32 v51, v156, v50
	s_waitcnt lgkmcnt(0)
	v_add_f32_e32 v50, v50, v51
	ds_bpermute_b32 v46, v157, v50
	s_waitcnt lgkmcnt(0)
	v_add_f32_e32 v46, v50, v46
	ds_bpermute_b32 v47, v158, v46
	s_waitcnt lgkmcnt(0)
	v_add_f32_e32 v46, v46, v47
	ds_bpermute_b32 v47, v159, v46
	s_waitcnt lgkmcnt(0)
	v_add_f32_e32 v46, v46, v47
	ds_bpermute_b32 v47, v160, v46
	s_waitcnt lgkmcnt(0)
	v_add_f32_e32 v46, v46, v47
	v_fmamk_f32 v46, v46, 0x3a800000, v161
	v_mul_f32_e32 v47, 0x4f800000, v46
	v_cmp_gt_f32_e32 vcc, s19, v46
	s_waitcnt vmcnt(0)
	v_pk_add_f32 v[36:37], v[36:37], 1.0 op_sel_hi:[1,0]
	v_cndmask_b32_e32 v42, v46, v47, vcc
	v_sqrt_f32_e32 v43, v42
	v_pk_add_f32 v[34:35], v[34:35], 1.0 op_sel_hi:[1,0]
	v_add_u32_e32 v44, -1, v43
	v_add_u32_e32 v45, 1, v43
	v_fma_f32 v46, -v44, v43, v42
	v_fma_f32 v47, -v45, v43, v42
	v_cmp_ge_f32_e64 s[6:7], 0, v46
	s_nop 1
	v_cndmask_b32_e64 v43, v43, v44, s[6:7]
	v_cmp_lt_f32_e64 s[6:7], 0, v47
	s_nop 1
	v_cndmask_b32_e64 v43, v43, v45, s[6:7]
	v_mul_f32_e32 v44, 0x37800000, v43
	v_cndmask_b32_e32 v43, v43, v44, vcc
	v_cmp_class_f32_e32 vcc, v42, v162
	s_nop 1
	v_cndmask_b32_e32 v42, v43, v42, vcc
	v_div_scale_f32 v43, s[6:7], v42, v42, 1.0
	v_rcp_f32_e32 v45, v43
	v_div_scale_f32 v44, vcc, 1.0, v42, 1.0
	v_fma_f32 v46, -v43, v45, 1.0
	v_fmac_f32_e32 v45, v46, v45
	v_mul_f32_e32 v46, v44, v45
	v_fma_f32 v47, -v43, v46, v44
	v_fmac_f32_e32 v46, v47, v45
	v_fma_f32 v43, -v43, v46, v44
	v_div_fmas_f32 v43, v43, v45, v46
	v_div_fixup_f32 v42, v43, v42, 1.0
	v_pk_mul_f32 v[32:33], v[32:33], v[42:43] op_sel_hi:[1,0]
	v_pk_mul_f32 v[30:31], v[30:31], v[42:43] op_sel_hi:[1,0]
	v_pk_mul_f32 v[32:33], v[32:33], v[4:5]
	v_pk_mul_f32 v[30:31], v[30:31], v[2:3]
	v_pk_fma_f32 v[32:33], v[32:33], v[36:37], v[40:41]
	v_pk_fma_f32 v[30:31], v[30:31], v[34:35], v[38:39]
	v_bfe_u32 v36, v32, 16, 1
	v_bfe_u32 v34, v30, 16, 1
	v_bfe_u32 v35, v31, 16, 1
	v_bfe_u32 v37, v33, 16, 1
	v_add3_u32 v30, v30, v34, s29
	v_add3_u32 v32, v32, v36, s29
	v_add3_u32 v31, v31, v35, s29
	v_add3_u32 v33, v33, v37, s29
	v_lshrrev_b32_e32 v30, 16, v30
	v_lshrrev_b32_e32 v32, 16, v32
	v_and_or_b32 v30, v31, s30, v30
	v_and_or_b32 v31, v33, s30, v32
	global_store_dwordx2 v[104:105], v[30:31], off offset:2048
	global_load_dwordx4 v[30:33], v[116:117], off
	s_nop 0
	global_load_dwordx4 v[34:37], v[106:107], off offset:1024
	v_pk_mul_f32 v[28:29], v[28:29], v[42:43] op_sel_hi:[1,0]
	v_pk_mul_f32 v[26:27], v[26:27], v[42:43] op_sel_hi:[1,0]
	v_pk_mul_f32 v[28:29], v[28:29], v[8:9]
	v_pk_mul_f32 v[26:27], v[26:27], v[6:7]
	v_lshl_add_u64 v[38:39], s[24:25], 0, v[98:99]
	v_pk_mul_f32 v[24:25], v[24:25], v[42:43] op_sel_hi:[1,0]
	v_pk_mul_f32 v[22:23], v[22:23], v[42:43] op_sel_hi:[1,0]
	v_pk_mul_f32 v[24:25], v[24:25], v[12:13]
	v_pk_mul_f32 v[22:23], v[22:23], v[10:11]
	v_pk_mul_f32 v[20:21], v[20:21], v[42:43] op_sel_hi:[1,0]
	v_pk_mul_f32 v[18:19], v[18:19], v[42:43] op_sel_hi:[1,0]
	v_pk_mul_f32 v[20:21], v[20:21], v[16:17]
	v_pk_mul_f32 v[18:19], v[18:19], v[14:15]
	s_waitcnt vmcnt(0) lgkmcnt(0)
	v_pk_add_f32 v[32:33], v[32:33], 1.0 op_sel_hi:[1,0]
	v_pk_add_f32 v[30:31], v[30:31], 1.0 op_sel_hi:[1,0]
	v_pk_fma_f32 v[28:29], v[28:29], v[32:33], v[36:37]
	v_pk_fma_f32 v[26:27], v[26:27], v[30:31], v[34:35]
	v_bfe_u32 v32, v28, 16, 1
	v_bfe_u32 v30, v26, 16, 1
	v_bfe_u32 v31, v27, 16, 1
	v_bfe_u32 v33, v29, 16, 1
	v_add3_u32 v26, v26, v30, s29
	v_add3_u32 v28, v28, v32, s29
	v_add3_u32 v27, v27, v31, s29
	v_add3_u32 v29, v29, v33, s29
	v_lshrrev_b32_e32 v26, 16, v26
	v_lshrrev_b32_e32 v28, 16, v28
	v_and_or_b32 v26, v27, s30, v26
	v_and_or_b32 v27, v29, s30, v28
	global_store_dwordx2 v[104:105], v[26:27], off offset:2560
	global_load_dwordx4 v[26:29], v[38:39], off
	s_nop 0
	global_load_dwordx4 v[30:33], v[106:107], off offset:2048
	v_lshl_add_u64 v[34:35], s[24:25], 0, v[100:101]
	s_waitcnt vmcnt(0) lgkmcnt(0)
	v_pk_add_f32 v[28:29], v[28:29], 1.0 op_sel_hi:[1,0]
	v_pk_add_f32 v[26:27], v[26:27], 1.0 op_sel_hi:[1,0]
	v_pk_fma_f32 v[24:25], v[24:25], v[28:29], v[32:33]
	v_pk_fma_f32 v[22:23], v[22:23], v[26:27], v[30:31]
	v_bfe_u32 v28, v24, 16, 1
	v_bfe_u32 v26, v22, 16, 1
	v_bfe_u32 v27, v23, 16, 1
	v_bfe_u32 v29, v25, 16, 1
	v_add3_u32 v22, v22, v26, s29
	v_add3_u32 v24, v24, v28, s29
	v_add3_u32 v23, v23, v27, s29
	v_add3_u32 v25, v25, v29, s29
	v_lshrrev_b32_e32 v22, 16, v22
	v_lshrrev_b32_e32 v24, 16, v24
	v_and_or_b32 v22, v23, s30, v22
	v_and_or_b32 v23, v25, s30, v24
	global_store_dwordx2 v[104:105], v[22:23], off offset:3072
	global_load_dwordx4 v[22:25], v[34:35], off
	s_nop 0
	global_load_dwordx4 v[26:29], v[106:107], off offset:3072
	s_waitcnt vmcnt(0) lgkmcnt(0)
	v_pk_add_f32 v[24:25], v[24:25], 1.0 op_sel_hi:[1,0]
	v_pk_add_f32 v[22:23], v[22:23], 1.0 op_sel_hi:[1,0]
	v_pk_fma_f32 v[20:21], v[20:21], v[24:25], v[28:29]
	v_pk_fma_f32 v[18:19], v[18:19], v[22:23], v[26:27]
	v_bfe_u32 v24, v20, 16, 1
	v_bfe_u32 v22, v18, 16, 1
	v_bfe_u32 v23, v19, 16, 1
	v_bfe_u32 v25, v21, 16, 1
	v_add3_u32 v18, v18, v22, s29
	v_add3_u32 v20, v20, v24, s29
	v_add3_u32 v19, v19, v23, s29
	v_add3_u32 v21, v21, v25, s29
	v_lshrrev_b32_e32 v18, 16, v18
	v_lshrrev_b32_e32 v20, 16, v20
	v_and_or_b32 v18, v19, s30, v18
	v_and_or_b32 v19, v21, s30, v20
	global_store_dwordx2 v[104:105], v[18:19], off offset:3584
	s_cbranch_scc1 .LBB0_842

.LBB0_863:
	v_mul_f32_e32 v154, 0xbfb8aa3b, v126
	v_exp_f32_e32 v155, v154
	v_mul_f32_e32 v162, 0xbfb8aa3b, v127
	v_exp_f32_e32 v162, v162
	v_lshl_or_b32 v156, s65, 7, v131
	v_add_f32_e32 v155, 1.0, v155
	v_div_scale_f32 v158, s[52:53], v155, v155, v126
	v_rcp_f32_e32 v159, v158
	v_div_scale_f32 v160, vcc, v126, v155, v126
	v_lshl_add_u32 v154, s50, 8, v1
	v_fma_f32 v161, -v158, v159, 1.0
	v_fmac_f32_e32 v159, v161, v159
	v_mul_f32_e32 v161, v160, v159
	v_fma_f32 v163, -v158, v161, v160
	v_fmac_f32_e32 v161, v163, v159
	v_fma_f32 v158, -v158, v161, v160
	v_add_f32_e32 v160, 1.0, v162
	v_div_scale_f32 v162, s[52:53], v160, v160, v127
	v_rcp_f32_e32 v163, v162
	v_div_fmas_f32 v158, v158, v159, v161
	v_div_fixup_f32 v126, v158, v155, v126
	v_mul_f32_e32 v122, v126, v122
	v_fma_f32 v126, -v162, v163, 1.0
	v_fmac_f32_e32 v163, v126, v163
	v_div_scale_f32 v126, vcc, v127, v160, v127
	v_mul_f32_e32 v155, v126, v163
	v_fma_f32 v158, -v162, v155, v126
	v_fmac_f32_e32 v155, v158, v163
	v_mul_f32_e32 v158, 0xbfb8aa3b, v128
	v_exp_f32_e32 v158, v158
	v_fma_f32 v126, -v162, v155, v126
	v_div_fmas_f32 v126, v126, v163, v155
	v_div_fixup_f32 v126, v126, v160, v127
	v_add_f32_e32 v155, 1.0, v158
	v_div_scale_f32 v158, s[52:53], v155, v155, v128
	v_rcp_f32_e32 v159, v158
	v_mul_f32_e32 v123, v126, v123
	v_mul_f32_e32 v127, 0xbfb8aa3b, v129
	v_cvt_pk_bf16_f32 v122, v122, v123
	v_fma_f32 v123, -v158, v159, 1.0
	v_exp_f32_e32 v127, v127
	v_fmac_f32_e32 v159, v123, v159
	v_div_scale_f32 v123, vcc, v128, v155, v128
	v_mul_f32_e32 v126, v123, v159
	v_fma_f32 v160, -v158, v126, v123
	v_fmac_f32_e32 v126, v160, v159
	v_add_f32_e32 v127, 1.0, v127
	v_fma_f32 v123, -v158, v126, v123
	v_div_scale_f32 v158, s[52:53], v127, v127, v129
	v_rcp_f32_e32 v160, v158
	v_div_fmas_f32 v123, v123, v159, v126
	v_div_fixup_f32 v123, v123, v155, v128
	v_mul_f32_e32 v123, v123, v124
	v_fma_f32 v124, -v158, v160, 1.0
	v_fmac_f32_e32 v160, v124, v160
	v_div_scale_f32 v124, vcc, v129, v127, v129
	v_mul_f32_e32 v126, v124, v160
	v_fma_f32 v128, -v158, v126, v124
	v_fmac_f32_e32 v126, v128, v160
	v_mul_f32_e32 v128, 0xbfb8aa3b, v118
	v_exp_f32_e32 v128, v128
	v_fma_f32 v124, -v158, v126, v124
	v_div_fmas_f32 v124, v124, v160, v126
	v_div_fixup_f32 v124, v124, v127, v129
	v_add_f32_e32 v126, 1.0, v128
	v_div_scale_f32 v128, s[52:53], v126, v126, v118
	v_rcp_f32_e32 v155, v128
	v_mul_f32_e32 v124, v124, v125
	v_mul_f32_e32 v127, 0xbfb8aa3b, v119
	v_cvt_pk_bf16_f32 v123, v123, v124
	v_fma_f32 v124, -v128, v155, 1.0
	v_exp_f32_e32 v127, v127
	v_fmac_f32_e32 v155, v124, v155
	v_div_scale_f32 v124, vcc, v118, v126, v118
	v_mul_f32_e32 v125, v124, v155
	v_fma_f32 v129, -v128, v125, v124
	v_fmac_f32_e32 v125, v129, v155
	v_add_f32_e32 v127, 1.0, v127
	v_fma_f32 v124, -v128, v125, v124
	v_div_scale_f32 v128, s[52:53], v127, v127, v119
	v_rcp_f32_e32 v129, v128
	v_div_fmas_f32 v124, v124, v155, v125
	v_div_fixup_f32 v118, v124, v126, v118
	v_mul_f32_e32 v114, v118, v114
	v_fma_f32 v118, -v128, v129, 1.0
	v_fmac_f32_e32 v129, v118, v129
	v_div_scale_f32 v118, vcc, v119, v127, v119
	v_mul_f32_e32 v124, v118, v129
	v_fma_f32 v125, -v128, v124, v118
	v_fmac_f32_e32 v124, v125, v129
	v_mul_f32_e32 v125, 0xbfb8aa3b, v120
	v_exp_f32_e32 v125, v125
	v_fma_f32 v118, -v128, v124, v118
	v_div_fmas_f32 v118, v118, v129, v124
	v_div_fixup_f32 v118, v118, v127, v119
	v_add_f32_e32 v125, 1.0, v125
	v_div_scale_f32 v126, s[52:53], v125, v125, v120
	v_rcp_f32_e32 v128, v126
	v_mul_f32_e32 v115, v118, v115
	v_mul_f32_e32 v118, 0xbfb8aa3b, v121
	v_exp_f32_e32 v118, v118
	v_cvt_pk_bf16_f32 v124, v114, v115
	v_fma_f32 v114, -v126, v128, 1.0
	v_fmac_f32_e32 v128, v114, v128
	v_div_scale_f32 v114, vcc, v120, v125, v120
	v_mul_f32_e32 v115, v114, v128
	v_fma_f32 v119, -v126, v115, v114
	v_add_f32_e32 v118, 1.0, v118
	v_fmac_f32_e32 v115, v119, v128
	v_div_scale_f32 v119, s[52:53], v118, v118, v121
	v_fma_f32 v114, -v126, v115, v114
	v_rcp_f32_e32 v126, v119
	v_div_fmas_f32 v114, v114, v128, v115
	v_div_fixup_f32 v114, v114, v125, v120
	v_mul_f32_e32 v114, v114, v116
	v_fma_f32 v115, -v119, v126, 1.0
	v_fmac_f32_e32 v126, v115, v126
	v_div_scale_f32 v115, vcc, v121, v118, v121
	v_mul_f32_e32 v116, v115, v126
	v_fma_f32 v120, -v119, v116, v115
	v_fmac_f32_e32 v116, v120, v126
	v_fma_f32 v115, -v119, v116, v115
	v_div_fmas_f32 v115, v115, v126, v116
	v_div_fixup_f32 v115, v115, v118, v121
	v_mul_f32_e32 v115, v115, v117
	v_cvt_pk_bf16_f32 v125, v114, v115
	v_mul_f32_e32 v114, 0xbfb8aa3b, v110
	v_exp_f32_e32 v116, v114
	v_ashrrev_i32_e32 v157, 31, v156
	v_mov_b64_e32 v[114:115], s[16:17]
	v_mad_i64_i32 v[118:119], s[52:53], v154, s64, v[114:115]
	v_add_f32_e32 v120, 1.0, v116
	v_div_scale_f32 v121, s[52:53], v120, v120, v110
	v_rcp_f32_e32 v126, v121
	v_lshlrev_b64 v[116:117], 1, v[156:157]
	v_lshl_add_u64 v[118:119], v[118:119], 0, v[116:117]
	global_store_dwordx4 v[118:119], v[122:125], off
	v_fma_f32 v118, -v121, v126, 1.0
	v_fmac_f32_e32 v126, v118, v126
	v_mul_f32_e32 v122, 0xbfb8aa3b, v111
	v_div_scale_f32 v118, vcc, v110, v120, v110
	v_exp_f32_e32 v122, v122
	v_mul_f32_e32 v119, v118, v126
	v_fma_f32 v123, -v121, v119, v118
	v_fmac_f32_e32 v119, v123, v126
	v_fma_f32 v118, -v121, v119, v118
	v_add_f32_e32 v121, 1.0, v122
	v_div_scale_f32 v122, s[52:53], v121, v121, v111
	v_rcp_f32_e32 v123, v122
	v_div_fmas_f32 v118, v118, v126, v119
	v_div_fixup_f32 v110, v118, v120, v110
	v_mul_f32_e32 v106, v110, v106
	v_fma_f32 v110, -v122, v123, 1.0
	v_fmac_f32_e32 v123, v110, v123
	v_div_scale_f32 v110, vcc, v111, v121, v111
	v_mul_f32_e32 v118, v110, v123
	v_fma_f32 v119, -v122, v118, v110
	v_fmac_f32_e32 v118, v119, v123
	v_mul_f32_e32 v119, 0xbfb8aa3b, v112
	v_exp_f32_e32 v119, v119
	v_fma_f32 v110, -v122, v118, v110
	v_div_fmas_f32 v110, v110, v123, v118
	v_div_fixup_f32 v110, v110, v121, v111
	v_add_f32_e32 v118, 1.0, v119
	v_div_scale_f32 v119, s[52:53], v118, v118, v112
	v_rcp_f32_e32 v120, v119
	v_mul_f32_e32 v107, v110, v107
	v_mul_f32_e32 v111, 0xbfb8aa3b, v113
	v_cvt_pk_bf16_f32 v106, v106, v107
	v_fma_f32 v107, -v119, v120, 1.0
	v_exp_f32_e32 v111, v111
	v_fmac_f32_e32 v120, v107, v120
	v_div_scale_f32 v107, vcc, v112, v118, v112
	v_mul_f32_e32 v110, v107, v120
	v_fma_f32 v121, -v119, v110, v107
	v_fmac_f32_e32 v110, v121, v120
	v_add_f32_e32 v111, 1.0, v111
	v_fma_f32 v107, -v119, v110, v107
	v_div_scale_f32 v119, s[52:53], v111, v111, v113
	v_rcp_f32_e32 v121, v119
	v_div_fmas_f32 v107, v107, v120, v110
	v_div_fixup_f32 v107, v107, v118, v112
	v_mul_f32_e32 v107, v107, v108
	v_fma_f32 v108, -v119, v121, 1.0
	v_fmac_f32_e32 v121, v108, v121
	v_div_scale_f32 v108, vcc, v113, v111, v113
	v_mul_f32_e32 v110, v108, v121
	v_fma_f32 v112, -v119, v110, v108
	v_fmac_f32_e32 v110, v112, v121
	v_mul_f32_e32 v112, 0xbfb8aa3b, v102
	v_exp_f32_e32 v112, v112
	v_fma_f32 v108, -v119, v110, v108
	v_div_fmas_f32 v108, v108, v121, v110
	v_div_fixup_f32 v108, v108, v111, v113
	v_add_f32_e32 v110, 1.0, v112
	v_div_scale_f32 v112, s[52:53], v110, v110, v102
	v_rcp_f32_e32 v118, v112
	v_mul_f32_e32 v108, v108, v109
	v_mul_f32_e32 v111, 0xbfb8aa3b, v103
	v_cvt_pk_bf16_f32 v107, v107, v108
	v_fma_f32 v108, -v112, v118, 1.0
	v_exp_f32_e32 v111, v111
	v_fmac_f32_e32 v118, v108, v118
	v_div_scale_f32 v108, vcc, v102, v110, v102
	v_mul_f32_e32 v109, v108, v118
	v_fma_f32 v113, -v112, v109, v108
	v_fmac_f32_e32 v109, v113, v118
	v_add_f32_e32 v111, 1.0, v111
	v_fma_f32 v108, -v112, v109, v108
	v_div_scale_f32 v112, s[52:53], v111, v111, v103
	v_rcp_f32_e32 v113, v112
	v_div_fmas_f32 v108, v108, v118, v109
	v_div_fixup_f32 v102, v108, v110, v102
	v_mul_f32_e32 v98, v102, v98
	v_fma_f32 v102, -v112, v113, 1.0
	v_fmac_f32_e32 v113, v102, v113
	v_div_scale_f32 v102, vcc, v103, v111, v103
	v_mul_f32_e32 v108, v102, v113
	v_fma_f32 v109, -v112, v108, v102
	v_fmac_f32_e32 v108, v109, v113
	v_mul_f32_e32 v109, 0xbfb8aa3b, v104
	v_exp_f32_e32 v109, v109
	v_fma_f32 v102, -v112, v108, v102
	v_div_fmas_f32 v102, v102, v113, v108
	v_div_fixup_f32 v102, v102, v111, v103
	v_add_f32_e32 v109, 1.0, v109
	v_div_scale_f32 v110, s[52:53], v109, v109, v104
	v_rcp_f32_e32 v112, v110
	v_mul_f32_e32 v99, v102, v99
	v_mul_f32_e32 v102, 0xbfb8aa3b, v105
	v_exp_f32_e32 v102, v102
	v_cvt_pk_bf16_f32 v108, v98, v99
	v_fma_f32 v98, -v110, v112, 1.0
	v_fmac_f32_e32 v112, v98, v112
	v_div_scale_f32 v98, vcc, v104, v109, v104
	v_mul_f32_e32 v99, v98, v112
	v_fma_f32 v103, -v110, v99, v98
	v_add_f32_e32 v102, 1.0, v102
	v_fmac_f32_e32 v99, v103, v112
	v_div_scale_f32 v103, s[52:53], v102, v102, v105
	v_fma_f32 v98, -v110, v99, v98
	v_rcp_f32_e32 v110, v103
	v_div_fmas_f32 v98, v98, v112, v99
	v_div_fixup_f32 v98, v98, v109, v104
	v_mul_f32_e32 v98, v98, v100
	v_fma_f32 v99, -v103, v110, 1.0
	v_fmac_f32_e32 v110, v99, v110
	v_div_scale_f32 v99, vcc, v105, v102, v105
	v_mul_f32_e32 v100, v99, v110
	v_fma_f32 v104, -v103, v100, v99
	v_fmac_f32_e32 v100, v104, v110
	v_fma_f32 v99, -v103, v100, v99
	v_div_fmas_f32 v99, v99, v110, v100
	v_mul_f32_e32 v100, 0xbfb8aa3b, v94
	v_exp_f32_e32 v100, v100
	v_div_fixup_f32 v99, v99, v102, v105
	v_mul_f32_e32 v99, v99, v101
	v_cvt_pk_bf16_f32 v109, v98, v99
	v_add_f32_e32 v100, 1.0, v100
	v_div_scale_f32 v101, s[52:53], v100, v100, v94
	v_rcp_f32_e32 v102, v101
	v_or_b32_e32 v98, 16, v154
	v_mad_i64_i32 v[98:99], s[52:53], v98, s64, v[114:115]
	v_lshl_add_u64 v[98:99], v[98:99], 0, v[116:117]
	global_store_dwordx4 v[98:99], v[106:109], off
	v_fma_f32 v98, -v101, v102, 1.0
	v_mul_f32_e32 v103, 0xbfb8aa3b, v95
	v_fmac_f32_e32 v102, v98, v102
	v_div_scale_f32 v98, vcc, v94, v100, v94
	v_exp_f32_e32 v103, v103
	v_mul_f32_e32 v99, v98, v102
	v_fma_f32 v104, -v101, v99, v98
	v_fmac_f32_e32 v99, v104, v102
	v_fma_f32 v98, -v101, v99, v98
	v_add_f32_e32 v101, 1.0, v103
	v_div_scale_f32 v103, s[52:53], v101, v101, v95
	v_rcp_f32_e32 v104, v103
	v_div_fmas_f32 v98, v98, v102, v99
	v_div_fixup_f32 v94, v98, v100, v94
	v_mul_f32_e32 v90, v94, v90
	v_fma_f32 v94, -v103, v104, 1.0
	v_fmac_f32_e32 v104, v94, v104
	v_div_scale_f32 v94, vcc, v95, v101, v95
	v_mul_f32_e32 v98, v94, v104
	v_fma_f32 v99, -v103, v98, v94
	v_fmac_f32_e32 v98, v99, v104
	v_mul_f32_e32 v99, 0xbfb8aa3b, v96
	v_exp_f32_e32 v99, v99
	v_fma_f32 v94, -v103, v98, v94
	v_div_fmas_f32 v94, v94, v104, v98
	v_div_fixup_f32 v94, v94, v101, v95
	v_add_f32_e32 v98, 1.0, v99
	v_div_scale_f32 v99, s[52:53], v98, v98, v96
	v_rcp_f32_e32 v100, v99
	v_mul_f32_e32 v91, v94, v91
	v_mul_f32_e32 v95, 0xbfb8aa3b, v97
	v_cvt_pk_bf16_f32 v90, v90, v91
	v_fma_f32 v91, -v99, v100, 1.0
	v_exp_f32_e32 v95, v95
	v_fmac_f32_e32 v100, v91, v100
	v_div_scale_f32 v91, vcc, v96, v98, v96
	v_mul_f32_e32 v94, v91, v100
	v_fma_f32 v101, -v99, v94, v91
	v_fmac_f32_e32 v94, v101, v100
	v_add_f32_e32 v95, 1.0, v95
	v_fma_f32 v91, -v99, v94, v91
	v_div_scale_f32 v99, s[52:53], v95, v95, v97
	v_rcp_f32_e32 v101, v99
	v_div_fmas_f32 v91, v91, v100, v94
	v_div_fixup_f32 v91, v91, v98, v96
	v_mul_f32_e32 v91, v91, v92
	v_fma_f32 v92, -v99, v101, 1.0
	v_fmac_f32_e32 v101, v92, v101
	v_div_scale_f32 v92, vcc, v97, v95, v97
	v_mul_f32_e32 v94, v92, v101
	v_fma_f32 v96, -v99, v94, v92
	v_fmac_f32_e32 v94, v96, v101
	v_mul_f32_e32 v96, 0xbfb8aa3b, v86
	v_exp_f32_e32 v96, v96
	v_fma_f32 v92, -v99, v94, v92
	v_div_fmas_f32 v92, v92, v101, v94
	v_div_fixup_f32 v92, v92, v95, v97
	v_add_f32_e32 v94, 1.0, v96
	v_div_scale_f32 v96, s[52:53], v94, v94, v86
	v_rcp_f32_e32 v98, v96
	v_mul_f32_e32 v92, v92, v93
	v_mul_f32_e32 v95, 0xbfb8aa3b, v87
	v_cvt_pk_bf16_f32 v91, v91, v92
	v_fma_f32 v92, -v96, v98, 1.0
	v_exp_f32_e32 v95, v95
	v_fmac_f32_e32 v98, v92, v98
	v_div_scale_f32 v92, vcc, v86, v94, v86
	v_mul_f32_e32 v93, v92, v98
	v_fma_f32 v97, -v96, v93, v92
	v_fmac_f32_e32 v93, v97, v98
	v_add_f32_e32 v95, 1.0, v95
	v_fma_f32 v92, -v96, v93, v92
	v_div_scale_f32 v96, s[52:53], v95, v95, v87
	v_rcp_f32_e32 v97, v96
	v_div_fmas_f32 v92, v92, v98, v93
	v_div_fixup_f32 v86, v92, v94, v86
	v_mul_f32_e32 v82, v86, v82
	v_fma_f32 v86, -v96, v97, 1.0
	v_fmac_f32_e32 v97, v86, v97
	v_div_scale_f32 v86, vcc, v87, v95, v87
	v_mul_f32_e32 v92, v86, v97
	v_fma_f32 v93, -v96, v92, v86
	v_fmac_f32_e32 v92, v93, v97
	v_mul_f32_e32 v93, 0xbfb8aa3b, v88
	v_exp_f32_e32 v93, v93
	v_fma_f32 v86, -v96, v92, v86
	v_div_fmas_f32 v86, v86, v97, v92
	v_div_fixup_f32 v86, v86, v95, v87
	v_add_f32_e32 v93, 1.0, v93
	v_div_scale_f32 v94, s[52:53], v93, v93, v88
	v_rcp_f32_e32 v96, v94
	v_mul_f32_e32 v83, v86, v83
	v_mul_f32_e32 v86, 0xbfb8aa3b, v89
	v_exp_f32_e32 v86, v86
	v_cvt_pk_bf16_f32 v92, v82, v83
	v_fma_f32 v82, -v94, v96, 1.0
	v_fmac_f32_e32 v96, v82, v96
	v_div_scale_f32 v82, vcc, v88, v93, v88
	v_mul_f32_e32 v83, v82, v96
	v_fma_f32 v87, -v94, v83, v82
	v_add_f32_e32 v86, 1.0, v86
	v_fmac_f32_e32 v83, v87, v96
	v_div_scale_f32 v87, s[52:53], v86, v86, v89
	v_fma_f32 v82, -v94, v83, v82
	v_rcp_f32_e32 v94, v87
	v_div_fmas_f32 v82, v82, v96, v83
	v_div_fixup_f32 v82, v82, v93, v88
	v_mul_f32_e32 v82, v82, v84
	v_fma_f32 v83, -v87, v94, 1.0
	v_fmac_f32_e32 v94, v83, v94
	v_div_scale_f32 v83, vcc, v89, v86, v89
	v_mul_f32_e32 v84, v83, v94
	v_fma_f32 v88, -v87, v84, v83
	v_fmac_f32_e32 v84, v88, v94
	v_fma_f32 v83, -v87, v84, v83
	v_div_fmas_f32 v83, v83, v94, v84
	v_mul_f32_e32 v84, 0xbfb8aa3b, v78
	v_exp_f32_e32 v84, v84
	v_div_fixup_f32 v83, v83, v86, v89
	v_mul_f32_e32 v83, v83, v85
	v_cvt_pk_bf16_f32 v93, v82, v83
	v_add_f32_e32 v84, 1.0, v84
	v_div_scale_f32 v85, s[52:53], v84, v84, v78
	v_rcp_f32_e32 v86, v85
	v_or_b32_e32 v82, 32, v154
	v_mad_i64_i32 v[82:83], s[52:53], v82, s64, v[114:115]
	v_lshl_add_u64 v[82:83], v[82:83], 0, v[116:117]
	global_store_dwordx4 v[82:83], v[90:93], off
	v_fma_f32 v82, -v85, v86, 1.0
	v_mul_f32_e32 v87, 0xbfb8aa3b, v79
	v_fmac_f32_e32 v86, v82, v86
	v_div_scale_f32 v82, vcc, v78, v84, v78
	v_exp_f32_e32 v87, v87
	v_mul_f32_e32 v83, v82, v86
	v_fma_f32 v88, -v85, v83, v82
	v_fmac_f32_e32 v83, v88, v86
	v_fma_f32 v82, -v85, v83, v82
	v_add_f32_e32 v85, 1.0, v87
	v_div_scale_f32 v87, s[52:53], v85, v85, v79
	v_rcp_f32_e32 v88, v87
	v_div_fmas_f32 v82, v82, v86, v83
	v_div_fixup_f32 v78, v82, v84, v78
	v_mul_f32_e32 v74, v78, v74
	v_fma_f32 v78, -v87, v88, 1.0
	v_fmac_f32_e32 v88, v78, v88
	v_div_scale_f32 v78, vcc, v79, v85, v79
	v_mul_f32_e32 v82, v78, v88
	v_fma_f32 v83, -v87, v82, v78
	v_fmac_f32_e32 v82, v83, v88
	v_mul_f32_e32 v83, 0xbfb8aa3b, v80
	v_exp_f32_e32 v83, v83
	v_fma_f32 v78, -v87, v82, v78
	v_div_fmas_f32 v78, v78, v88, v82
	v_div_fixup_f32 v78, v78, v85, v79
	v_add_f32_e32 v82, 1.0, v83
	v_div_scale_f32 v83, s[52:53], v82, v82, v80
	v_rcp_f32_e32 v84, v83
	v_mul_f32_e32 v75, v78, v75
	v_mul_f32_e32 v79, 0xbfb8aa3b, v81
	v_cvt_pk_bf16_f32 v74, v74, v75
	v_fma_f32 v75, -v83, v84, 1.0
	v_exp_f32_e32 v79, v79
	v_fmac_f32_e32 v84, v75, v84
	v_div_scale_f32 v75, vcc, v80, v82, v80
	v_mul_f32_e32 v78, v75, v84
	v_fma_f32 v85, -v83, v78, v75
	v_fmac_f32_e32 v78, v85, v84
	v_add_f32_e32 v79, 1.0, v79
	v_fma_f32 v75, -v83, v78, v75
	v_div_scale_f32 v83, s[52:53], v79, v79, v81
	v_rcp_f32_e32 v85, v83
	v_div_fmas_f32 v75, v75, v84, v78
	v_div_fixup_f32 v75, v75, v82, v80
	v_mul_f32_e32 v75, v75, v76
	v_fma_f32 v76, -v83, v85, 1.0
	v_fmac_f32_e32 v85, v76, v85
	v_div_scale_f32 v76, vcc, v81, v79, v81
	v_mul_f32_e32 v78, v76, v85
	v_fma_f32 v80, -v83, v78, v76
	v_fmac_f32_e32 v78, v80, v85
	v_mul_f32_e32 v80, 0xbfb8aa3b, v70
	v_exp_f32_e32 v80, v80
	v_fma_f32 v76, -v83, v78, v76
	v_div_fmas_f32 v76, v76, v85, v78
	v_div_fixup_f32 v76, v76, v79, v81
	v_add_f32_e32 v78, 1.0, v80
	v_div_scale_f32 v80, s[52:53], v78, v78, v70
	v_rcp_f32_e32 v82, v80
	v_mul_f32_e32 v76, v76, v77
	v_mul_f32_e32 v79, 0xbfb8aa3b, v71
	v_cvt_pk_bf16_f32 v75, v75, v76
	v_fma_f32 v76, -v80, v82, 1.0
	v_exp_f32_e32 v79, v79
	v_fmac_f32_e32 v82, v76, v82
	v_div_scale_f32 v76, vcc, v70, v78, v70
	v_mul_f32_e32 v77, v76, v82
	v_fma_f32 v81, -v80, v77, v76
	v_fmac_f32_e32 v77, v81, v82
	v_add_f32_e32 v79, 1.0, v79
	v_fma_f32 v76, -v80, v77, v76
	v_div_scale_f32 v80, s[52:53], v79, v79, v71
	v_rcp_f32_e32 v81, v80
	v_div_fmas_f32 v76, v76, v82, v77
	v_div_fixup_f32 v70, v76, v78, v70
	v_mul_f32_e32 v66, v70, v66
	v_fma_f32 v70, -v80, v81, 1.0
	v_fmac_f32_e32 v81, v70, v81
	v_div_scale_f32 v70, vcc, v71, v79, v71
	v_mul_f32_e32 v76, v70, v81
	v_fma_f32 v77, -v80, v76, v70
	v_fmac_f32_e32 v76, v77, v81
	v_mul_f32_e32 v77, 0xbfb8aa3b, v72
	v_exp_f32_e32 v77, v77
	v_fma_f32 v70, -v80, v76, v70
	v_div_fmas_f32 v70, v70, v81, v76
	v_div_fixup_f32 v70, v70, v79, v71
	v_add_f32_e32 v77, 1.0, v77
	v_div_scale_f32 v78, s[52:53], v77, v77, v72
	v_rcp_f32_e32 v80, v78
	v_mul_f32_e32 v67, v70, v67
	v_mul_f32_e32 v70, 0xbfb8aa3b, v73
	v_exp_f32_e32 v70, v70
	v_cvt_pk_bf16_f32 v76, v66, v67
	v_fma_f32 v66, -v78, v80, 1.0
	v_fmac_f32_e32 v80, v66, v80
	v_div_scale_f32 v66, vcc, v72, v77, v72
	v_mul_f32_e32 v67, v66, v80
	v_fma_f32 v71, -v78, v67, v66
	v_add_f32_e32 v70, 1.0, v70
	v_fmac_f32_e32 v67, v71, v80
	v_div_scale_f32 v71, s[52:53], v70, v70, v73
	v_fma_f32 v66, -v78, v67, v66
	v_rcp_f32_e32 v78, v71
	v_div_fmas_f32 v66, v66, v80, v67
	v_div_fixup_f32 v66, v66, v77, v72
	v_mul_f32_e32 v66, v66, v68
	v_fma_f32 v67, -v71, v78, 1.0
	v_fmac_f32_e32 v78, v67, v78
	v_div_scale_f32 v67, vcc, v73, v70, v73
	v_mul_f32_e32 v68, v67, v78
	v_fma_f32 v72, -v71, v68, v67
	v_fmac_f32_e32 v68, v72, v78
	v_fma_f32 v67, -v71, v68, v67
	v_div_fmas_f32 v67, v67, v78, v68
	v_div_fixup_f32 v67, v67, v70, v73
	v_mul_f32_e32 v67, v67, v69
	v_cvt_pk_bf16_f32 v77, v66, v67
	v_mul_f32_e32 v66, 0xbfb8aa3b, v62
	v_exp_f32_e32 v68, v66
	v_or_b32_e32 v66, 48, v154
	v_mad_i64_i32 v[66:67], s[52:53], v66, s64, v[114:115]
	v_add_f32_e32 v68, 1.0, v68
	v_div_scale_f32 v69, s[52:53], v68, v68, v62
	v_rcp_f32_e32 v70, v69
	v_lshl_add_u64 v[66:67], v[66:67], 0, v[116:117]
	global_store_dwordx4 v[66:67], v[74:77], off
	v_mul_f32_e32 v72, 0xbfb8aa3b, v63
	v_fma_f32 v67, -v69, v70, 1.0
	v_fmac_f32_e32 v70, v67, v70
	v_div_scale_f32 v67, vcc, v62, v68, v62
	v_exp_f32_e32 v72, v72
	v_mul_f32_e32 v71, v67, v70
	v_fma_f32 v73, -v69, v71, v67
	v_fmac_f32_e32 v71, v73, v70
	v_fma_f32 v67, -v69, v71, v67
	v_add_f32_e32 v69, 1.0, v72
	v_div_scale_f32 v72, s[52:53], v69, v69, v63
	v_rcp_f32_e32 v73, v72
	v_div_fmas_f32 v67, v67, v70, v71
	v_div_fixup_f32 v62, v67, v68, v62
	v_mul_f32_e32 v58, v62, v58
	v_fma_f32 v62, -v72, v73, 1.0
	v_fmac_f32_e32 v73, v62, v73
	v_div_scale_f32 v62, vcc, v63, v69, v63
	v_mul_f32_e32 v67, v62, v73
	v_fma_f32 v68, -v72, v67, v62
	v_fmac_f32_e32 v67, v68, v73
	v_mul_f32_e32 v68, 0xbfb8aa3b, v64
	v_exp_f32_e32 v68, v68
	v_fma_f32 v62, -v72, v67, v62
	v_div_fmas_f32 v62, v62, v73, v67
	v_div_fixup_f32 v62, v62, v69, v63
	v_add_f32_e32 v67, 1.0, v68
	v_div_scale_f32 v68, s[52:53], v67, v67, v64
	v_rcp_f32_e32 v70, v68
	v_mul_f32_e32 v59, v62, v59
	v_mul_f32_e32 v63, 0xbfb8aa3b, v65
	v_cvt_pk_bf16_f32 v58, v58, v59
	v_fma_f32 v59, -v68, v70, 1.0
	v_exp_f32_e32 v63, v63
	v_fmac_f32_e32 v70, v59, v70
	v_div_scale_f32 v59, vcc, v64, v67, v64
	v_mul_f32_e32 v62, v59, v70
	v_fma_f32 v69, -v68, v62, v59
	v_fmac_f32_e32 v62, v69, v70
	v_add_f32_e32 v63, 1.0, v63
	v_fma_f32 v59, -v68, v62, v59
	v_div_scale_f32 v68, s[52:53], v63, v63, v65
	v_rcp_f32_e32 v69, v68
	v_div_fmas_f32 v59, v59, v70, v62
	v_div_fixup_f32 v59, v59, v67, v64
	v_mul_f32_e32 v59, v59, v60
	v_fma_f32 v60, -v68, v69, 1.0
	v_fmac_f32_e32 v69, v60, v69
	v_div_scale_f32 v60, vcc, v65, v63, v65
	v_mul_f32_e32 v62, v60, v69
	v_fma_f32 v64, -v68, v62, v60
	v_fmac_f32_e32 v62, v64, v69
	v_mul_f32_e32 v64, 0xbfb8aa3b, v54
	v_exp_f32_e32 v64, v64
	v_fma_f32 v60, -v68, v62, v60
	v_div_fmas_f32 v60, v60, v69, v62
	v_div_fixup_f32 v60, v60, v63, v65
	v_add_f32_e32 v62, 1.0, v64
	v_div_scale_f32 v64, s[52:53], v62, v62, v54
	v_rcp_f32_e32 v67, v64
	v_mul_f32_e32 v60, v60, v61
	v_mul_f32_e32 v63, 0xbfb8aa3b, v55
	v_cvt_pk_bf16_f32 v59, v59, v60
	v_fma_f32 v60, -v64, v67, 1.0
	v_exp_f32_e32 v63, v63
	v_fmac_f32_e32 v67, v60, v67
	v_div_scale_f32 v60, vcc, v54, v62, v54
	v_mul_f32_e32 v61, v60, v67
	v_fma_f32 v65, -v64, v61, v60
	v_fmac_f32_e32 v61, v65, v67
	v_add_f32_e32 v63, 1.0, v63
	v_fma_f32 v60, -v64, v61, v60
	v_div_scale_f32 v64, s[52:53], v63, v63, v55
	v_rcp_f32_e32 v65, v64
	v_div_fmas_f32 v60, v60, v67, v61
	v_div_fixup_f32 v54, v60, v62, v54
	v_mul_f32_e32 v50, v54, v50
	v_fma_f32 v54, -v64, v65, 1.0
	v_fmac_f32_e32 v65, v54, v65
	v_div_scale_f32 v54, vcc, v55, v63, v55
	v_mul_f32_e32 v60, v54, v65
	v_fma_f32 v61, -v64, v60, v54
	v_fmac_f32_e32 v60, v61, v65
	v_mul_f32_e32 v61, 0xbfb8aa3b, v56
	v_exp_f32_e32 v61, v61
	v_fma_f32 v54, -v64, v60, v54
	v_div_fmas_f32 v54, v54, v65, v60
	v_div_fixup_f32 v54, v54, v63, v55
	v_add_f32_e32 v61, 1.0, v61
	v_div_scale_f32 v62, s[52:53], v61, v61, v56
	v_rcp_f32_e32 v64, v62
	v_mul_f32_e32 v51, v54, v51
	v_mul_f32_e32 v54, 0xbfb8aa3b, v57
	v_exp_f32_e32 v54, v54
	v_cvt_pk_bf16_f32 v60, v50, v51
	v_fma_f32 v50, -v62, v64, 1.0
	v_fmac_f32_e32 v64, v50, v64
	v_div_scale_f32 v50, vcc, v56, v61, v56
	v_mul_f32_e32 v51, v50, v64
	v_fma_f32 v55, -v62, v51, v50
	v_add_f32_e32 v54, 1.0, v54
	v_fmac_f32_e32 v51, v55, v64
	v_div_scale_f32 v55, s[52:53], v54, v54, v57
	v_fma_f32 v50, -v62, v51, v50
	v_rcp_f32_e32 v62, v55
	v_div_fmas_f32 v50, v50, v64, v51
	v_div_fixup_f32 v50, v50, v61, v56
	v_mul_f32_e32 v50, v50, v52
	v_fma_f32 v51, -v55, v62, 1.0
	v_fmac_f32_e32 v62, v51, v62
	v_div_scale_f32 v51, vcc, v57, v54, v57
	v_mul_f32_e32 v52, v51, v62
	v_fma_f32 v56, -v55, v52, v51
	v_fmac_f32_e32 v52, v56, v62
	v_fma_f32 v51, -v55, v52, v51
	v_div_fmas_f32 v51, v51, v62, v52
	v_mul_f32_e32 v52, 0xbfb8aa3b, v46
	v_exp_f32_e32 v52, v52
	v_div_fixup_f32 v51, v51, v54, v57
	v_mul_f32_e32 v51, v51, v53
	v_add_u32_e32 v66, 0x80, v154
	v_add_f32_e32 v52, 1.0, v52
	v_div_scale_f32 v53, s[52:53], v52, v52, v46
	v_rcp_f32_e32 v54, v53
	v_cvt_pk_bf16_f32 v61, v50, v51
	v_mad_i64_i32 v[50:51], s[52:53], v66, s64, v[114:115]
	v_lshl_add_u64 v[50:51], v[50:51], 0, v[116:117]
	global_store_dwordx4 v[50:51], v[58:61], off
	v_fma_f32 v50, -v53, v54, 1.0
	v_mul_f32_e32 v55, 0xbfb8aa3b, v47
	v_fmac_f32_e32 v54, v50, v54
	v_div_scale_f32 v50, vcc, v46, v52, v46
	v_exp_f32_e32 v55, v55
	v_mul_f32_e32 v51, v50, v54
	v_fma_f32 v56, -v53, v51, v50
	v_fmac_f32_e32 v51, v56, v54
	v_fma_f32 v50, -v53, v51, v50
	v_add_f32_e32 v53, 1.0, v55
	v_div_scale_f32 v55, s[52:53], v53, v53, v47
	v_rcp_f32_e32 v56, v55
	v_div_fmas_f32 v50, v50, v54, v51
	v_div_fixup_f32 v46, v50, v52, v46
	v_mul_f32_e32 v42, v46, v42
	v_fma_f32 v46, -v55, v56, 1.0
	v_fmac_f32_e32 v56, v46, v56
	v_div_scale_f32 v46, vcc, v47, v53, v47
	v_mul_f32_e32 v50, v46, v56
	v_fma_f32 v51, -v55, v50, v46
	v_fmac_f32_e32 v50, v51, v56
	v_mul_f32_e32 v51, 0xbfb8aa3b, v48
	v_exp_f32_e32 v51, v51
	v_fma_f32 v46, -v55, v50, v46
	v_div_fmas_f32 v46, v46, v56, v50
	v_div_fixup_f32 v46, v46, v53, v47
	v_add_f32_e32 v50, 1.0, v51
	v_div_scale_f32 v51, s[52:53], v50, v50, v48
	v_rcp_f32_e32 v52, v51
	v_mul_f32_e32 v43, v46, v43
	v_mul_f32_e32 v47, 0xbfb8aa3b, v49
	v_cvt_pk_bf16_f32 v42, v42, v43
	v_fma_f32 v43, -v51, v52, 1.0
	v_exp_f32_e32 v47, v47
	v_fmac_f32_e32 v52, v43, v52
	v_div_scale_f32 v43, vcc, v48, v50, v48
	v_mul_f32_e32 v46, v43, v52
	v_fma_f32 v53, -v51, v46, v43
	v_fmac_f32_e32 v46, v53, v52
	v_add_f32_e32 v47, 1.0, v47
	v_fma_f32 v43, -v51, v46, v43
	v_div_scale_f32 v51, s[52:53], v47, v47, v49
	v_rcp_f32_e32 v53, v51
	v_div_fmas_f32 v43, v43, v52, v46
	v_div_fixup_f32 v43, v43, v50, v48
	v_mul_f32_e32 v43, v43, v44
	v_fma_f32 v44, -v51, v53, 1.0
	v_fmac_f32_e32 v53, v44, v53
	v_div_scale_f32 v44, vcc, v49, v47, v49
	v_mul_f32_e32 v46, v44, v53
	v_fma_f32 v48, -v51, v46, v44
	v_fmac_f32_e32 v46, v48, v53
	v_mul_f32_e32 v48, 0xbfb8aa3b, v38
	v_exp_f32_e32 v48, v48
	v_fma_f32 v44, -v51, v46, v44
	v_div_fmas_f32 v44, v44, v53, v46
	v_div_fixup_f32 v44, v44, v47, v49
	v_add_f32_e32 v46, 1.0, v48
	v_div_scale_f32 v48, s[52:53], v46, v46, v38
	v_rcp_f32_e32 v50, v48
	v_mul_f32_e32 v44, v44, v45
	v_mul_f32_e32 v47, 0xbfb8aa3b, v39
	v_cvt_pk_bf16_f32 v43, v43, v44
	v_fma_f32 v44, -v48, v50, 1.0
	v_exp_f32_e32 v47, v47
	v_fmac_f32_e32 v50, v44, v50
	v_div_scale_f32 v44, vcc, v38, v46, v38
	v_mul_f32_e32 v45, v44, v50
	v_fma_f32 v49, -v48, v45, v44
	v_fmac_f32_e32 v45, v49, v50
	v_add_f32_e32 v47, 1.0, v47
	v_fma_f32 v44, -v48, v45, v44
	v_div_scale_f32 v48, s[52:53], v47, v47, v39
	v_rcp_f32_e32 v49, v48
	v_div_fmas_f32 v44, v44, v50, v45
	v_div_fixup_f32 v38, v44, v46, v38
	v_mul_f32_e32 v34, v38, v34
	v_fma_f32 v38, -v48, v49, 1.0
	v_fmac_f32_e32 v49, v38, v49
	v_div_scale_f32 v38, vcc, v39, v47, v39
	v_mul_f32_e32 v44, v38, v49
	v_fma_f32 v45, -v48, v44, v38
	v_fmac_f32_e32 v44, v45, v49
	v_mul_f32_e32 v45, 0xbfb8aa3b, v40
	v_exp_f32_e32 v45, v45
	v_fma_f32 v38, -v48, v44, v38
	v_div_fmas_f32 v38, v38, v49, v44
	v_div_fixup_f32 v38, v38, v47, v39
	v_add_f32_e32 v45, 1.0, v45
	v_div_scale_f32 v46, s[52:53], v45, v45, v40
	v_rcp_f32_e32 v48, v46
	v_mul_f32_e32 v35, v38, v35
	v_mul_f32_e32 v38, 0xbfb8aa3b, v41
	v_exp_f32_e32 v38, v38
	v_cvt_pk_bf16_f32 v44, v34, v35
	v_fma_f32 v34, -v46, v48, 1.0
	v_fmac_f32_e32 v48, v34, v48
	v_div_scale_f32 v34, vcc, v40, v45, v40
	v_mul_f32_e32 v35, v34, v48
	v_fma_f32 v39, -v46, v35, v34
	v_add_f32_e32 v38, 1.0, v38
	v_fmac_f32_e32 v35, v39, v48
	v_div_scale_f32 v39, s[52:53], v38, v38, v41
	v_fma_f32 v34, -v46, v35, v34
	v_rcp_f32_e32 v46, v39
	v_div_fmas_f32 v34, v34, v48, v35
	v_div_fixup_f32 v34, v34, v45, v40
	v_mul_f32_e32 v34, v34, v36
	v_fma_f32 v35, -v39, v46, 1.0
	v_fmac_f32_e32 v46, v35, v46
	v_div_scale_f32 v35, vcc, v41, v38, v41
	v_mul_f32_e32 v36, v35, v46
	v_fma_f32 v40, -v39, v36, v35
	v_fmac_f32_e32 v36, v40, v46
	v_fma_f32 v35, -v39, v36, v35
	v_div_fmas_f32 v35, v35, v46, v36
	v_mul_f32_e32 v36, 0xbfb8aa3b, v30
	v_exp_f32_e32 v36, v36
	v_div_fixup_f32 v35, v35, v38, v41
	v_mul_f32_e32 v35, v35, v37
	v_cvt_pk_bf16_f32 v45, v34, v35
	v_add_f32_e32 v36, 1.0, v36
	v_div_scale_f32 v37, s[52:53], v36, v36, v30
	v_rcp_f32_e32 v38, v37
	v_add_u32_e32 v34, 0x90, v154
	v_mad_i64_i32 v[34:35], s[52:53], v34, s64, v[114:115]
	v_lshl_add_u64 v[34:35], v[34:35], 0, v[116:117]
	global_store_dwordx4 v[34:35], v[42:45], off
	v_fma_f32 v34, -v37, v38, 1.0
	v_mul_f32_e32 v39, 0xbfb8aa3b, v31
	v_fmac_f32_e32 v38, v34, v38
	v_div_scale_f32 v34, vcc, v30, v36, v30
	v_exp_f32_e32 v39, v39
	v_mul_f32_e32 v35, v34, v38
	v_fma_f32 v40, -v37, v35, v34
	v_fmac_f32_e32 v35, v40, v38
	v_fma_f32 v34, -v37, v35, v34
	v_add_f32_e32 v37, 1.0, v39
	v_div_scale_f32 v39, s[52:53], v37, v37, v31
	v_rcp_f32_e32 v40, v39
	v_div_fmas_f32 v34, v34, v38, v35
	v_div_fixup_f32 v30, v34, v36, v30
	v_mul_f32_e32 v26, v30, v26
	v_fma_f32 v30, -v39, v40, 1.0
	v_fmac_f32_e32 v40, v30, v40
	v_div_scale_f32 v30, vcc, v31, v37, v31
	v_mul_f32_e32 v34, v30, v40
	v_fma_f32 v35, -v39, v34, v30
	v_fmac_f32_e32 v34, v35, v40
	v_mul_f32_e32 v35, 0xbfb8aa3b, v32
	v_exp_f32_e32 v35, v35
	v_fma_f32 v30, -v39, v34, v30
	v_div_fmas_f32 v30, v30, v40, v34
	v_div_fixup_f32 v30, v30, v37, v31
	v_add_f32_e32 v34, 1.0, v35
	v_div_scale_f32 v35, s[52:53], v34, v34, v32
	v_rcp_f32_e32 v36, v35
	v_mul_f32_e32 v27, v30, v27
	v_mul_f32_e32 v31, 0xbfb8aa3b, v33
	v_cvt_pk_bf16_f32 v26, v26, v27
	v_fma_f32 v27, -v35, v36, 1.0
	v_exp_f32_e32 v31, v31
	v_fmac_f32_e32 v36, v27, v36
	v_div_scale_f32 v27, vcc, v32, v34, v32
	v_mul_f32_e32 v30, v27, v36
	v_fma_f32 v37, -v35, v30, v27
	v_fmac_f32_e32 v30, v37, v36
	v_add_f32_e32 v31, 1.0, v31
	v_fma_f32 v27, -v35, v30, v27
	v_div_scale_f32 v35, s[52:53], v31, v31, v33
	v_rcp_f32_e32 v37, v35
	v_div_fmas_f32 v27, v27, v36, v30
	v_div_fixup_f32 v27, v27, v34, v32
	v_mul_f32_e32 v27, v27, v28
	v_fma_f32 v28, -v35, v37, 1.0
	v_fmac_f32_e32 v37, v28, v37
	v_div_scale_f32 v28, vcc, v33, v31, v33
	v_mul_f32_e32 v30, v28, v37
	v_fma_f32 v32, -v35, v30, v28
	v_fmac_f32_e32 v30, v32, v37
	v_mul_f32_e32 v32, 0xbfb8aa3b, v22
	v_exp_f32_e32 v32, v32
	v_fma_f32 v28, -v35, v30, v28
	v_div_fmas_f32 v28, v28, v37, v30
	v_div_fixup_f32 v28, v28, v31, v33
	v_add_f32_e32 v30, 1.0, v32
	v_div_scale_f32 v32, s[52:53], v30, v30, v22
	v_rcp_f32_e32 v34, v32
	v_mul_f32_e32 v28, v28, v29
	v_mul_f32_e32 v31, 0xbfb8aa3b, v23
	v_cvt_pk_bf16_f32 v27, v27, v28
	v_fma_f32 v28, -v32, v34, 1.0
	v_exp_f32_e32 v31, v31
	v_fmac_f32_e32 v34, v28, v34
	v_div_scale_f32 v28, vcc, v22, v30, v22
	v_mul_f32_e32 v29, v28, v34
	v_fma_f32 v33, -v32, v29, v28
	v_fmac_f32_e32 v29, v33, v34
	v_add_f32_e32 v31, 1.0, v31
	v_fma_f32 v28, -v32, v29, v28
	v_div_scale_f32 v32, s[52:53], v31, v31, v23
	v_rcp_f32_e32 v33, v32
	v_div_fmas_f32 v28, v28, v34, v29
	v_div_fixup_f32 v22, v28, v30, v22
	v_mul_f32_e32 v18, v22, v18
	v_fma_f32 v22, -v32, v33, 1.0
	v_fmac_f32_e32 v33, v22, v33
	v_div_scale_f32 v22, vcc, v23, v31, v23
	v_mul_f32_e32 v28, v22, v33
	v_fma_f32 v29, -v32, v28, v22
	v_fmac_f32_e32 v28, v29, v33
	v_mul_f32_e32 v29, 0xbfb8aa3b, v24
	v_exp_f32_e32 v29, v29
	v_fma_f32 v22, -v32, v28, v22
	v_div_fmas_f32 v22, v22, v33, v28
	v_div_fixup_f32 v22, v22, v31, v23
	v_add_f32_e32 v29, 1.0, v29
	v_div_scale_f32 v30, s[52:53], v29, v29, v24
	v_rcp_f32_e32 v32, v30
	v_mul_f32_e32 v19, v22, v19
	v_mul_f32_e32 v22, 0xbfb8aa3b, v25
	v_exp_f32_e32 v22, v22
	v_cvt_pk_bf16_f32 v28, v18, v19
	v_fma_f32 v18, -v30, v32, 1.0
	v_fmac_f32_e32 v32, v18, v32
	v_div_scale_f32 v18, vcc, v24, v29, v24
	v_mul_f32_e32 v19, v18, v32
	v_fma_f32 v23, -v30, v19, v18
	v_add_f32_e32 v22, 1.0, v22
	v_fmac_f32_e32 v19, v23, v32
	v_div_scale_f32 v23, s[52:53], v22, v22, v25
	v_fma_f32 v18, -v30, v19, v18
	v_rcp_f32_e32 v30, v23
	v_div_fmas_f32 v18, v18, v32, v19
	v_div_fixup_f32 v18, v18, v29, v24
	v_mul_f32_e32 v18, v18, v20
	v_fma_f32 v19, -v23, v30, 1.0
	v_fmac_f32_e32 v30, v19, v30
	v_div_scale_f32 v19, vcc, v25, v22, v25
	v_mul_f32_e32 v20, v19, v30
	v_fma_f32 v24, -v23, v20, v19
	v_fmac_f32_e32 v20, v24, v30
	v_fma_f32 v19, -v23, v20, v19
	v_div_fmas_f32 v19, v19, v30, v20
	v_mul_f32_e32 v20, 0xbfb8aa3b, v14
	v_exp_f32_e32 v20, v20
	v_div_fixup_f32 v19, v19, v22, v25
	v_mul_f32_e32 v19, v19, v21
	v_cvt_pk_bf16_f32 v29, v18, v19
	v_add_f32_e32 v20, 1.0, v20
	v_div_scale_f32 v21, s[52:53], v20, v20, v14
	v_rcp_f32_e32 v22, v21
	v_add_u32_e32 v18, 0xa0, v154
	v_mad_i64_i32 v[18:19], s[52:53], v18, s64, v[114:115]
	v_lshl_add_u64 v[18:19], v[18:19], 0, v[116:117]
	global_store_dwordx4 v[18:19], v[26:29], off
	v_fma_f32 v18, -v21, v22, 1.0
	v_mul_f32_e32 v23, 0xbfb8aa3b, v15
	v_fmac_f32_e32 v22, v18, v22
	v_div_scale_f32 v18, vcc, v14, v20, v14
	v_exp_f32_e32 v23, v23
	v_mul_f32_e32 v19, v18, v22
	v_fma_f32 v24, -v21, v19, v18
	v_fmac_f32_e32 v19, v24, v22
	v_fma_f32 v18, -v21, v19, v18
	v_add_f32_e32 v21, 1.0, v23
	v_div_scale_f32 v23, s[52:53], v21, v21, v15
	v_rcp_f32_e32 v24, v23
	v_div_fmas_f32 v18, v18, v22, v19
	v_div_fixup_f32 v14, v18, v20, v14
	v_mul_f32_e32 v10, v14, v10
	v_fma_f32 v14, -v23, v24, 1.0
	v_fmac_f32_e32 v24, v14, v24
	v_div_scale_f32 v14, vcc, v15, v21, v15
	v_mul_f32_e32 v18, v14, v24
	v_fma_f32 v19, -v23, v18, v14
	v_fmac_f32_e32 v18, v19, v24
	v_mul_f32_e32 v19, 0xbfb8aa3b, v16
	v_exp_f32_e32 v19, v19
	v_fma_f32 v14, -v23, v18, v14
	v_div_fmas_f32 v14, v14, v24, v18
	v_div_fixup_f32 v14, v14, v21, v15
	v_add_f32_e32 v18, 1.0, v19
	v_div_scale_f32 v19, s[52:53], v18, v18, v16
	v_rcp_f32_e32 v20, v19
	v_mul_f32_e32 v11, v14, v11
	v_mul_f32_e32 v15, 0xbfb8aa3b, v17
	v_cvt_pk_bf16_f32 v10, v10, v11
	v_fma_f32 v11, -v19, v20, 1.0
	v_exp_f32_e32 v15, v15
	v_fmac_f32_e32 v20, v11, v20
	v_div_scale_f32 v11, vcc, v16, v18, v16
	v_mul_f32_e32 v14, v11, v20
	v_fma_f32 v21, -v19, v14, v11
	v_fmac_f32_e32 v14, v21, v20
	v_add_f32_e32 v15, 1.0, v15
	v_fma_f32 v11, -v19, v14, v11
	v_div_scale_f32 v19, s[52:53], v15, v15, v17
	v_rcp_f32_e32 v21, v19
	v_div_fmas_f32 v11, v11, v20, v14
	v_div_fixup_f32 v11, v11, v18, v16
	v_mul_f32_e32 v11, v11, v12
	v_fma_f32 v12, -v19, v21, 1.0
	v_fmac_f32_e32 v21, v12, v21
	v_div_scale_f32 v12, vcc, v17, v15, v17
	v_mul_f32_e32 v14, v12, v21
	v_fma_f32 v16, -v19, v14, v12
	v_fmac_f32_e32 v14, v16, v21
	v_mul_f32_e32 v16, 0xbfb8aa3b, v6
	v_exp_f32_e32 v16, v16
	v_fma_f32 v12, -v19, v14, v12
	v_div_fmas_f32 v12, v12, v21, v14
	v_div_fixup_f32 v12, v12, v15, v17
	v_add_f32_e32 v14, 1.0, v16
	v_div_scale_f32 v16, s[52:53], v14, v14, v6
	v_rcp_f32_e32 v18, v16
	v_mul_f32_e32 v12, v12, v13
	v_mul_f32_e32 v15, 0xbfb8aa3b, v7
	v_cvt_pk_bf16_f32 v11, v11, v12
	v_fma_f32 v12, -v16, v18, 1.0
	v_exp_f32_e32 v15, v15
	v_fmac_f32_e32 v18, v12, v18
	v_div_scale_f32 v12, vcc, v6, v14, v6
	v_mul_f32_e32 v13, v12, v18
	v_fma_f32 v17, -v16, v13, v12
	v_fmac_f32_e32 v13, v17, v18
	v_add_f32_e32 v15, 1.0, v15
	v_fma_f32 v12, -v16, v13, v12
	v_div_scale_f32 v16, s[52:53], v15, v15, v7
	v_rcp_f32_e32 v17, v16
	v_div_fmas_f32 v12, v12, v18, v13
	v_div_fixup_f32 v6, v12, v14, v6
	v_mul_f32_e32 v2, v6, v2
	v_fma_f32 v6, -v16, v17, 1.0
	v_fmac_f32_e32 v17, v6, v17
	v_div_scale_f32 v6, vcc, v7, v15, v7
	v_mul_f32_e32 v12, v6, v17
	v_fma_f32 v13, -v16, v12, v6
	v_fmac_f32_e32 v12, v13, v17
	v_mul_f32_e32 v13, 0xbfb8aa3b, v8
	v_exp_f32_e32 v13, v13
	v_fma_f32 v6, -v16, v12, v6
	v_div_fmas_f32 v6, v6, v17, v12
	v_div_fixup_f32 v6, v6, v15, v7
	v_add_f32_e32 v13, 1.0, v13
	v_div_scale_f32 v14, s[52:53], v13, v13, v8
	v_rcp_f32_e32 v16, v14
	v_mul_f32_e32 v3, v6, v3
	v_mul_f32_e32 v6, 0xbfb8aa3b, v9
	v_exp_f32_e32 v6, v6
	v_cvt_pk_bf16_f32 v12, v2, v3
	v_fma_f32 v2, -v14, v16, 1.0
	v_fmac_f32_e32 v16, v2, v16
	v_div_scale_f32 v2, vcc, v8, v13, v8
	v_mul_f32_e32 v3, v2, v16
	v_fma_f32 v7, -v14, v3, v2
	v_add_f32_e32 v6, 1.0, v6
	v_fmac_f32_e32 v3, v7, v16
	v_div_scale_f32 v7, s[52:53], v6, v6, v9
	v_fma_f32 v2, -v14, v3, v2
	v_rcp_f32_e32 v14, v7
	v_div_fmas_f32 v2, v2, v16, v3
	v_div_fixup_f32 v2, v2, v13, v8
	v_mul_f32_e32 v2, v2, v4
	v_fma_f32 v3, -v7, v14, 1.0
	v_fmac_f32_e32 v14, v3, v14
	v_div_scale_f32 v3, vcc, v9, v6, v9
	v_mul_f32_e32 v4, v3, v14
	v_fma_f32 v8, -v7, v4, v3
	v_fmac_f32_e32 v4, v8, v14
	v_fma_f32 v3, -v7, v4, v3
	v_div_fmas_f32 v3, v3, v14, v4
	v_div_fixup_f32 v3, v3, v6, v9
	v_mul_f32_e32 v3, v3, v5
	v_cvt_pk_bf16_f32 v13, v2, v3
	v_add_u32_e32 v2, 0xb0, v154
	v_mad_i64_i32 v[2:3], s[52:53], v2, s64, v[114:115]
	v_lshl_add_u64 v[2:3], v[2:3], 0, v[116:117]
	s_andn2_b64 vcc, exec, s[46:47]
	s_mov_b64 s[46:47], -1
	global_store_dwordx4 v[2:3], v[10:13], off
	s_cbranch_vccnz .LBB0_852
	s_andn2_b64 vcc, exec, s[6:7]
	s_cbranch_vccnz .LBB0_851
	s_barrier
	s_branch .LBB0_851

.LBB0_880:
	s_lshl_b32 s4, s28, 2
	s_add_u32 s4, s38, s4
	s_addc_u32 s7, s39, 0
	s_add_u32 s6, s4, 0x16000000
	s_addc_u32 s7, s7, 0
	s_mov_b32 s5, 0
	v_add_u32_e32 v130, 0x4000, v144
	s_movk_i32 s9, 0x3000
	v_mov_b64_e32 v[138:139], s[6:7]
	s_lshl_b32 s4, s3, 8
	v_mad_i64_i32 v[140:141], s[6:7], v130, s9, v[138:139]
	s_lshl_b64 s[4:5], s[4:5], 2
	v_lshl_add_u64 v[140:141], v[140:141], 0, s[4:5]
	v_mov_b32_e32 v133, 0
	v_lshl_add_u64 v[140:141], v[140:141], 0, v[132:133]
	global_store_dwordx4 v[140:141], v[126:129], off
	global_store_dwordx4 v[140:141], v[122:125], off offset:64
	global_store_dwordx4 v[140:141], v[106:109], off offset:512
	global_store_dwordx4 v[140:141], v[98:101], off offset:576
	s_ashr_i32 s13, s23, 6
	v_and_b32_e32 v131, 63, v1
	v_add_u32_e32 v98, 0x4010, v144
	v_mad_i64_i32 v[98:99], s[6:7], v98, s9, v[138:139]
	v_lshl_add_u64 v[98:99], v[98:99], 0, s[4:5]
	v_lshl_add_u64 v[98:99], v[98:99], 0, v[132:133]
	global_store_dwordx4 v[98:99], v[118:121], off
	global_store_dwordx4 v[98:99], v[114:117], off offset:64
	global_store_dwordx4 v[98:99], v[90:93], off offset:512
	global_store_dwordx4 v[98:99], v[82:85], off offset:576
	s_add_i32 s8, s13, s2
	s_nop 0
	v_add_u32_e32 v82, 0x4020, v144
	v_mad_i64_i32 v[82:83], s[6:7], v82, s9, v[138:139]
	v_lshl_add_u64 v[82:83], v[82:83], 0, s[4:5]
	v_lshl_add_u64 v[82:83], v[82:83], 0, v[132:133]
	global_store_dwordx4 v[82:83], v[110:113], off
	global_store_dwordx4 v[82:83], v[102:105], off offset:64
	global_store_dwordx4 v[82:83], v[78:81], off offset:512
	global_store_dwordx4 v[82:83], v[74:77], off offset:576
	s_nop 1
	v_add_u32_e32 v74, 0x4030, v144
	v_mad_i64_i32 v[74:75], s[6:7], v74, s9, v[138:139]
	v_lshl_add_u64 v[74:75], v[74:75], 0, s[4:5]
	v_lshl_add_u64 v[74:75], v[74:75], 0, v[132:133]
	global_store_dwordx4 v[74:75], v[94:97], off
	global_store_dwordx4 v[74:75], v[86:89], off offset:64
	global_store_dwordx4 v[74:75], v[70:73], off offset:512
	global_store_dwordx4 v[74:75], v[66:69], off offset:576
	s_nop 1
	v_add_u32_e32 v66, 0x4080, v144
	v_mad_i64_i32 v[66:67], s[6:7], v66, s9, v[138:139]
	v_lshl_add_u64 v[66:67], v[66:67], 0, s[4:5]
	v_lshl_add_u64 v[66:67], v[66:67], 0, v[132:133]
	global_store_dwordx4 v[66:67], v[62:65], off
	global_store_dwordx4 v[66:67], v[58:61], off offset:64
	global_store_dwordx4 v[66:67], v[42:45], off offset:512
	global_store_dwordx4 v[66:67], v[34:37], off offset:576
	s_nop 1
	v_add_u32_e32 v34, 0x4090, v144
	v_mad_i64_i32 v[34:35], s[6:7], v34, s9, v[138:139]
	v_lshl_add_u64 v[34:35], v[34:35], 0, s[4:5]
	v_lshl_add_u64 v[34:35], v[34:35], 0, v[132:133]
	global_store_dwordx4 v[34:35], v[54:57], off
	global_store_dwordx4 v[34:35], v[50:53], off offset:64
	global_store_dwordx4 v[34:35], v[26:29], off offset:512
	global_store_dwordx4 v[34:35], v[18:21], off offset:576
	s_nop 1
	v_add_u32_e32 v18, 0x40a0, v144
	v_mad_i64_i32 v[18:19], s[6:7], v18, s9, v[138:139]
	v_lshl_add_u64 v[18:19], v[18:19], 0, s[4:5]
	v_lshl_add_u64 v[18:19], v[18:19], 0, v[132:133]
	global_store_dwordx4 v[18:19], v[46:49], off
	global_store_dwordx4 v[18:19], v[38:41], off offset:64
	global_store_dwordx4 v[18:19], v[14:17], off offset:512
	global_store_dwordx4 v[18:19], v[10:13], off offset:576
	s_nop 1
	v_add_u32_e32 v10, 0x40b0, v144
	v_mad_i64_i32 v[10:11], s[6:7], v10, s9, v[138:139]
	v_lshl_add_u64 v[10:11], v[10:11], 0, s[4:5]
	v_lshl_add_u64 v[10:11], v[10:11], 0, v[132:133]
	global_store_dwordx4 v[10:11], v[30:33], off
	global_store_dwordx4 v[10:11], v[22:25], off offset:64
	global_store_dwordx4 v[10:11], v[6:9], off offset:512
	global_store_dwordx4 v[10:11], v[2:5], off offset:576
	s_waitcnt vmcnt(0)
	s_barrier

.LBB0_1002:
	s_or_b64 exec, exec, s[10:11]
	v_mov_b32_e32 v130, v0
	v_mov_b64_e32 v[2:3], s[0:1]
	s_barrier
	global_load_dwordx2 v[2:3], v[2:3], off offset:88 sc0 sc1
	s_waitcnt vmcnt(0)
	v_readfirstlane_b32 s3, v130
	s_ashr_i32 s3, s3, 6
	s_add_i32 s12, s3, s2
	s_cmp_gt_i32 s3, 15
	v_and_b32_e32 v132, 63, v130
	s_cbranch_scc1 .LBB0_1005
	v_mov_b32_e32 v91, 0
	v_lshlrev_b32_e32 v90, 4, v132
	s_waitcnt lgkmcnt(0)
	v_lshl_add_u64 v[2:3], v[2:3], 0, v[90:91]
	s_movk_i32 s2, 0x1000
	v_add_co_u32_e32 v18, vcc, s2, v2
	v_mbcnt_lo_u32_b32 v1, -1, 0
	s_nop 0
	v_addc_co_u32_e32 v19, vcc, 0, v3, vcc
	global_load_dwordx4 v[2:5], v[18:19], off
	global_load_dwordx4 v[6:9], v[18:19], off offset:1024
	global_load_dwordx4 v[10:13], v[18:19], off offset:2048
	global_load_dwordx4 v[14:17], v[18:19], off offset:3072
	v_mbcnt_hi_u32_b32 v18, -1, v1
	v_and_b32_e32 v1, 64, v18
	v_add_u32_e32 v19, 64, v1
	v_xor_b32_e32 v1, 1, v18
	v_cmp_lt_i32_e32 vcc, v1, v19
	v_xor_b32_e32 v20, 2, v18
	s_lshl_b32 s7, s27, 8
	v_cndmask_b32_e32 v1, v18, v1, vcc
	v_cmp_lt_i32_e32 vcc, v20, v19
	s_lshl_b32 s2, s26, 6
	s_add_i32 s8, s7, s2
	v_cndmask_b32_e32 v20, v18, v20, vcc
	v_lshlrev_b32_e32 v131, 2, v20
	v_xor_b32_e32 v20, 4, v18
	v_cmp_lt_i32_e32 vcc, v20, v19
	s_lshl_b32 s9, s3, 2
	s_add_i32 s6, s9, s8
	v_cndmask_b32_e32 v20, v18, v20, vcc
	v_lshlrev_b32_e32 v133, 2, v20
	v_xor_b32_e32 v20, 8, v18
	v_cmp_lt_i32_e32 vcc, v20, v19
	s_add_u32 s2, s38, 0x5803000
	s_addc_u32 s13, s39, 0
	v_cndmask_b32_e32 v20, v18, v20, vcc
	v_lshlrev_b32_e32 v152, 2, v20
	v_xor_b32_e32 v20, 16, v18
	v_cmp_lt_i32_e32 vcc, v20, v19
	s_lshl_b32 s5, s5, 6
	s_add_i32 s5, s7, s5
	v_cndmask_b32_e32 v20, v18, v20, vcc
	v_lshlrev_b32_e32 v153, 2, v20
	v_xor_b32_e32 v20, 32, v18
	v_cmp_lt_i32_e32 vcc, v20, v19
	s_add_i32 s5, s5, s9
	s_lshl_b32 s4, s4, 6
	v_cndmask_b32_e32 v18, v18, v20, vcc
	s_sub_i32 s4, s5, s4
	s_ashr_i32 s7, s6, 31
	v_lshlrev_b32_e32 v154, 2, v18
	s_or_b32 s22, s8, 32
	v_lshlrev_b32_e32 v18, 2, v132
	s_sub_i32 s8, s4, 32
	s_lshl_b64 s[4:5], s[6:7], 11
	v_or_b32_e32 v20, 0x100, v18
	v_or_b32_e32 v22, 0x200, v18
	v_or_b32_e32 v24, 0x300, v18
	v_lshl_or_b32 v92, v132, 3, s4
	v_mov_b32_e32 v93, s5
	s_lshl_b64 s[4:5], s[6:7], 12
	v_lshlrev_b32_e32 v1, 2, v1
	v_or_b32_e32 v94, s4, v90
	v_mov_b32_e32 v95, s5
	v_mov_b32_e32 v155, 0x358637bd
	s_mov_b32 s4, 0xf800000
	v_mov_b32_e32 v156, 0x260
	v_lshlrev_b32_e32 v90, 2, v18
	s_movk_i32 s5, 0x7fff
	s_mov_b32 s23, 0xffff0000
	s_mov_b32 s24, 0xba00000
	v_lshlrev_b32_e32 v96, 2, v20
	v_mov_b32_e32 v97, v91
	v_lshlrev_b32_e32 v98, 2, v22
	v_mov_b32_e32 v99, v91
	v_lshlrev_b32_e32 v100, 2, v24
	v_mov_b32_e32 v101, v91
	s_mov_b32 s25, 0xba01000
	s_mov_b64 s[16:17], 0x10000
	s_mov_b64 s[18:19], 0x20000
.LBB0_1004:
	v_lshl_add_u64 v[18:19], s[38:39], 0, v[94:95]
	v_lshl_add_u64 v[22:23], s[38:39], 0, v[92:93]
	v_add_co_u32_e32 v20, vcc, 0x7800000, v18
	v_add_co_u32_e64 v102, s[6:7], s24, v22
	s_nop 0
	v_addc_co_u32_e32 v21, vcc, 0, v19, vcc
	v_addc_co_u32_e64 v103, s[6:7], 0, v23, s[6:7]
	v_add_co_u32_e64 v104, s[6:7], s25, v22
	v_add_co_u32_e32 v22, vcc, 0x7801000, v18
	s_nop 0
	v_addc_co_u32_e64 v105, s[6:7], 0, v23, s[6:7]
	global_load_dwordx4 v[78:81], v[20:21], off
	global_load_dwordx4 v[74:77], v[20:21], off offset:1024
	global_load_dwordx4 v[70:73], v[20:21], off offset:2048
	global_load_dwordx4 v[66:69], v[20:21], off offset:3072
	v_addc_co_u32_e32 v23, vcc, 0, v19, vcc
	v_add_co_u32_e32 v20, vcc, 0x7802000, v18
	global_load_dwordx4 v[62:65], v[22:23], off
	global_load_dwordx4 v[58:61], v[22:23], off offset:1024
	global_load_dwordx4 v[54:57], v[22:23], off offset:2048
	global_load_dwordx4 v[50:53], v[22:23], off offset:3072
	v_addc_co_u32_e32 v21, vcc, 0, v19, vcc
	global_load_dwordx4 v[46:49], v[20:21], off
	global_load_dwordx4 v[42:45], v[20:21], off offset:1024
	global_load_dwordx4 v[38:41], v[20:21], off offset:2048
	global_load_dwordx4 v[34:37], v[20:21], off offset:3072
	v_add_co_u32_e32 v82, vcc, 0x7803000, v18
	s_add_i32 s26, s8, 32
	s_nop 0
	v_addc_co_u32_e32 v83, vcc, 0, v19, vcc
	global_load_dwordx4 v[30:33], v[82:83], off
	global_load_dwordx4 v[26:29], v[82:83], off offset:1024
	global_load_dwordx4 v[22:25], v[82:83], off offset:2048
	global_load_dwordx4 v[18:21], v[82:83], off offset:3072
	s_add_i32 s10, s8, 0xffffc022
	s_ashr_i32 s9, s26, 13
	s_cmpk_lt_i32 s26, 0x4000
	s_cselect_b32 s6, s9, s10
	s_mul_hi_i32 s7, s6, 0x9000
	s_mul_i32 s6, s6, 0x9000
	s_add_u32 s6, s2, s6
	s_addc_u32 s7, s13, s7
	s_add_u32 s10, s6, 0x1000
	s_addc_u32 s11, s7, 0
	v_lshl_add_u64 v[124:125], s[6:7], 0, v[90:91]
	v_lshl_add_u64 v[86:87], s[10:11], 0, v[90:91]
	global_load_dwordx4 v[82:85], v[124:125], off
	s_add_i32 s6, s8, 0xffffc023
	global_load_dwordx4 v[86:89], v[86:87], off
	s_cmpk_lt_i32 s26, 0x3fff
	s_cselect_b32 s6, s9, s6
	s_mul_hi_i32 s7, s6, 0x9000
	s_mul_i32 s6, s6, 0x9000
	s_add_u32 s6, s2, s6
	s_addc_u32 s7, s13, s7
	v_lshl_add_u64 v[138:139], s[10:11], 0, v[96:97]
	v_lshl_add_u64 v[134:135], s[10:11], 0, v[98:99]
	v_lshl_add_u64 v[128:129], s[10:11], 0, v[100:101]
	s_add_u32 s10, s6, 0x1000
	v_lshl_add_u64 v[110:111], s[6:7], 0, v[90:91]
	s_addc_u32 s11, s7, 0
	s_add_i32 s6, s8, 0xffffc024
	s_cmpk_lt_i32 s26, 0x3ffe
	s_cselect_b32 s6, s9, s6
	s_mul_hi_i32 s7, s6, 0x9000
	s_mul_i32 s6, s6, 0x9000
	v_lshl_add_u64 v[126:127], s[10:11], 0, v[90:91]
	v_lshl_add_u64 v[120:121], s[10:11], 0, v[96:97]
	v_lshl_add_u64 v[116:117], s[10:11], 0, v[98:99]
	v_lshl_add_u64 v[112:113], s[10:11], 0, v[100:101]
	s_add_u32 s10, s2, s6
	s_addc_u32 s11, s13, s7
	s_add_u32 s6, s10, 0x1000
	s_addc_u32 s7, s11, 0
	s_addk_i32 s8, 0xc025
	s_cmpk_lt_i32 s26, 0x3ffd
	v_lshl_add_u64 v[142:143], s[6:7], 0, v[90:91]
	v_lshl_add_u64 v[140:141], s[6:7], 0, v[96:97]
	v_lshl_add_u64 v[136:137], s[6:7], 0, v[98:99]
	v_lshl_add_u64 v[122:123], s[6:7], 0, v[100:101]
	s_cselect_b32 s6, s9, s8
	s_mul_hi_i32 s7, s6, 0x9000
	s_mul_i32 s6, s6, 0x9000
	s_add_u32 s6, s2, s6
	s_addc_u32 s7, s13, s7
	s_add_u32 s20, s6, 0x1000
	v_lshl_add_u64 v[106:107], s[6:7], 0, v[90:91]
	s_addc_u32 s21, s7, 0
	v_lshl_add_u64 v[108:109], s[10:11], 0, v[90:91]
	v_lshl_add_u64 v[118:119], s[20:21], 0, v[90:91]
	v_lshl_add_u64 v[114:115], s[20:21], 0, v[96:97]
	v_lshl_add_u64 v[92:93], v[92:93], 0, s[16:17]
	v_lshl_add_u64 v[94:95], v[94:95], 0, s[18:19]
	s_cmp_lt_i32 s26, s22
	s_waitcnt vmcnt(0) lgkmcnt(0)
	v_pk_mul_f32 v[144:145], v[80:81], v[80:81]
	v_pk_mul_f32 v[146:147], v[78:79], v[78:79]
	v_pk_mul_f32 v[148:149], v[76:77], v[76:77]
	v_pk_mul_f32 v[150:151], v[74:75], v[74:75]
	v_mul_f32_e32 v158, v71, v71
	v_mul_f32_e32 v160, v73, v73
	v_pk_mov_b32 v[162:163], v[146:147], v[144:145] op_sel:[1,0]
	v_mov_b32_e32 v147, v145
	v_pk_mov_b32 v[144:145], v[150:151], v[148:149] op_sel:[1,0]
	v_mov_b32_e32 v151, v149
	v_mul_f32_e32 v171, v68, v68
	v_mul_f32_e32 v173, v69, v69
	v_pk_fma_f32 v[148:149], v[70:71], v[70:71], v[158:159] op_sel_hi:[1,1,0]
	v_pk_fma_f32 v[158:159], v[72:73], v[72:73], v[160:161] op_sel_hi:[1,1,0]
	v_pk_mul_f32 v[160:161], v[64:65], v[64:65]
	v_pk_mul_f32 v[164:165], v[62:63], v[62:63]
	v_pk_mul_f32 v[166:167], v[60:61], v[60:61]
	v_pk_mul_f32 v[168:169], v[58:59], v[58:59]
	v_mul_f32_e32 v170, v55, v55
	v_mul_f32_e32 v172, v57, v57
	v_pk_add_f32 v[146:147], v[162:163], v[146:147]
	v_pk_add_f32 v[144:145], v[144:145], v[150:151]
	v_mul_f32_e32 v157, v66, v66
	v_mul_f32_e32 v181, v67, v67
	v_mov_b32_e32 v149, v171
	v_mov_b32_e32 v159, v173
	v_pk_mov_b32 v[150:151], v[164:165], v[160:161] op_sel:[1,0]
	v_mov_b32_e32 v165, v161
	v_pk_mov_b32 v[160:161], v[168:169], v[166:167] op_sel:[1,0]
	v_mov_b32_e32 v169, v167
	v_pk_fma_f32 v[162:163], v[54:55], v[54:55], v[170:171] op_sel_hi:[1,1,0]
	v_pk_fma_f32 v[166:167], v[56:57], v[56:57], v[172:173] op_sel_hi:[1,1,0]
	v_pk_mul_f32 v[170:171], v[48:49], v[48:49]
	v_pk_mul_f32 v[172:173], v[46:47], v[46:47]
	v_pk_add_f32 v[182:183], v[146:147], v[146:147] op_sel:[0,1] op_sel_hi:[1,0]
	v_pk_add_f32 v[184:185], v[144:145], v[144:145] op_sel:[0,1] op_sel_hi:[1,0]
	v_mul_f32_e32 v179, v52, v52
	v_pk_mul_f32 v[174:175], v[44:45], v[44:45]
	v_pk_mul_f32 v[176:177], v[42:43], v[42:43]
	v_mul_f32_e32 v178, v39, v39
	v_mul_f32_e32 v180, v41, v41
	v_pk_add_f32 v[158:159], v[148:149], v[158:159]
	v_pk_add_f32 v[144:145], v[150:151], v[164:165]
	v_pk_add_f32 v[146:147], v[160:161], v[168:169]
	v_pk_mov_b32 v[148:149], v[172:173], v[170:171] op_sel:[1,0]
	v_mov_b32_e32 v173, v171
	v_mov_b32_e32 v183, v157
	v_mov_b32_e32 v185, v181
	v_mul_f32_e32 v187, v50, v50
	v_mul_f32_e32 v192, v51, v51
	v_mul_f32_e32 v186, v53, v53
	v_mul_f32_e32 v195, v36, v36
	v_mul_f32_e32 v196, v37, v37
	v_pk_mov_b32 v[150:151], v[176:177], v[174:175] op_sel:[1,0]
	v_mov_b32_e32 v177, v175
	v_pk_fma_f32 v[160:161], v[38:39], v[38:39], v[178:179] op_sel_hi:[1,1,0]
	v_pk_fma_f32 v[164:165], v[40:41], v[40:41], v[180:181] op_sel_hi:[1,1,0]
	v_pk_add_f32 v[188:189], v[144:145], v[144:145] op_sel:[0,1] op_sel_hi:[1,0]
	v_pk_add_f32 v[190:191], v[146:147], v[146:147] op_sel:[0,1] op_sel_hi:[1,0]
	v_pk_add_f32 v[148:149], v[148:149], v[172:173]
	v_pk_add_f32 v[172:173], v[182:183], v[184:185]
	v_mov_b32_e32 v163, v179
	v_mov_b32_e32 v167, v186
	v_pk_mul_f32 v[168:169], v[32:33], v[32:33]
	v_pk_mul_f32 v[170:171], v[30:31], v[30:31]
	v_pk_mul_f32 v[174:175], v[28:29], v[28:29]
	v_pk_mul_f32 v[178:179], v[26:27], v[26:27]
	v_pk_add_f32 v[150:151], v[150:151], v[176:177]
	v_mov_b32_e32 v161, v195
	v_mov_b32_e32 v165, v196
	v_mov_b32_e32 v189, v187
	v_mov_b32_e32 v191, v192
	v_pk_add_f32 v[158:159], v[172:173], v[158:159]
	v_mul_f32_e32 v193, v34, v34
	v_mul_f32_e32 v194, v35, v35
	v_pk_add_f32 v[162:163], v[162:163], v[166:167]
	v_pk_mov_b32 v[166:167], v[170:171], v[168:169] op_sel:[1,0]
	v_mov_b32_e32 v171, v169
	v_pk_mov_b32 v[168:169], v[178:179], v[174:175] op_sel:[1,0]
	v_mov_b32_e32 v179, v175
	v_pk_add_f32 v[174:175], v[148:149], v[148:149] op_sel:[0,1] op_sel_hi:[1,0]
	v_pk_add_f32 v[176:177], v[150:151], v[150:151] op_sel:[0,1] op_sel_hi:[1,0]
	v_pk_add_f32 v[160:161], v[160:161], v[164:165]
	v_pk_add_f32 v[164:165], v[188:189], v[190:191]
	v_add_f32_e32 v157, v158, v159
	v_mov_b32_e32 v175, v193
	v_mov_b32_e32 v177, v194
	v_pk_add_f32 v[158:159], v[164:165], v[162:163]
	ds_bpermute_b32 v165, v1, v157
	v_pk_add_f32 v[162:163], v[174:175], v[176:177]
	v_add_f32_e32 v164, v158, v159
	v_pk_add_f32 v[158:159], v[162:163], v[160:161]
	ds_bpermute_b32 v160, v1, v164
	v_add_f32_e32 v158, v158, v159
	ds_bpermute_b32 v159, v1, v158
	s_waitcnt lgkmcnt(2)
	v_add_f32_e32 v157, v157, v165
	ds_bpermute_b32 v161, v131, v157
	s_waitcnt lgkmcnt(2)
	v_add_f32_e32 v160, v164, v160
	ds_bpermute_b32 v162, v131, v160
	s_waitcnt lgkmcnt(2)
	v_add_f32_e32 v158, v158, v159
	ds_bpermute_b32 v159, v131, v158
	s_waitcnt lgkmcnt(2)
	v_add_f32_e32 v157, v157, v161
	ds_bpermute_b32 v161, v133, v157
	s_waitcnt lgkmcnt(2)
	v_add_f32_e32 v160, v160, v162
	ds_bpermute_b32 v162, v133, v160
	s_waitcnt lgkmcnt(2)
	v_add_f32_e32 v158, v158, v159
	ds_bpermute_b32 v159, v133, v158
	s_waitcnt lgkmcnt(2)
	v_add_f32_e32 v157, v157, v161
	ds_bpermute_b32 v161, v152, v157
	s_waitcnt lgkmcnt(2)
	v_add_f32_e32 v160, v160, v162
	ds_bpermute_b32 v162, v152, v160
	s_waitcnt lgkmcnt(2)
	v_add_f32_e32 v158, v158, v159
	ds_bpermute_b32 v159, v152, v158
	s_waitcnt lgkmcnt(2)
	v_add_f32_e32 v157, v157, v161
	ds_bpermute_b32 v161, v153, v157
	s_waitcnt lgkmcnt(2)
	v_add_f32_e32 v160, v160, v162
	ds_bpermute_b32 v162, v153, v160
	s_waitcnt lgkmcnt(2)
	v_add_f32_e32 v158, v158, v159
	ds_bpermute_b32 v159, v153, v158
	s_waitcnt lgkmcnt(2)
	v_add_f32_e32 v157, v157, v161
	ds_bpermute_b32 v161, v154, v157
	s_waitcnt lgkmcnt(2)
	v_add_f32_e32 v160, v160, v162
	ds_bpermute_b32 v162, v154, v160
	s_waitcnt lgkmcnt(2)
	v_add_f32_e32 v158, v158, v159
	ds_bpermute_b32 v159, v154, v158
	s_waitcnt lgkmcnt(2)
	v_add_f32_e32 v157, v157, v161
	v_fmamk_f32 v157, v157, 0x3a800000, v155
	s_waitcnt lgkmcnt(1)
	v_add_f32_e32 v160, v160, v162
	v_mul_f32_e32 v161, 0x4f800000, v157
	v_cmp_gt_f32_e32 vcc, s4, v157
	v_fmamk_f32 v160, v160, 0x3a800000, v155
	s_waitcnt lgkmcnt(0)
	v_add_f32_e32 v158, v158, v159
	v_cndmask_b32_e32 v157, v157, v161, vcc
	v_mul_f32_e32 v159, 0x4f800000, v160
	v_cmp_gt_f32_e64 s[6:7], s4, v160
	v_sqrt_f32_e32 v161, v157
	v_fmamk_f32 v158, v158, 0x3a800000, v155
	v_cndmask_b32_e64 v159, v160, v159, s[6:7]
	v_mul_f32_e32 v160, 0x4f800000, v158
	v_cmp_gt_f32_e64 s[8:9], s4, v158
	v_sqrt_f32_e32 v162, v159
	v_add_u32_e32 v163, -1, v161
	v_cndmask_b32_e64 v158, v158, v160, s[8:9]
	v_sqrt_f32_e32 v160, v158
	v_add_u32_e32 v164, 1, v161
	v_fma_f32 v165, -v163, v161, v157
	v_pk_add_f32 v[148:149], v[166:167], v[170:171]
	v_fma_f32 v166, -v164, v161, v157
	v_add_u32_e32 v167, -1, v162
	v_cmp_ge_f32_e64 s[10:11], 0, v165
	v_pk_add_f32 v[150:151], v[168:169], v[178:179]
	v_add_u32_e32 v168, 1, v162
	v_cndmask_b32_e64 v161, v161, v163, s[10:11]
	v_fma_f32 v163, -v167, v162, v159
	v_cmp_lt_f32_e64 s[10:11], 0, v166
	v_fma_f32 v165, -v168, v162, v159
	v_add_u32_e32 v169, -1, v160
	v_cndmask_b32_e64 v161, v161, v164, s[10:11]
	v_cmp_ge_f32_e64 s[10:11], 0, v163
	v_add_u32_e32 v170, 1, v160
	v_fma_f32 v163, -v169, v160, v158
	v_cndmask_b32_e64 v162, v162, v167, s[10:11]
	v_cmp_lt_f32_e64 s[10:11], 0, v165
	v_fma_f32 v164, -v170, v160, v158
	v_mul_f32_e32 v165, 0x37800000, v161
	v_cndmask_b32_e64 v162, v162, v168, s[10:11]
	v_cmp_ge_f32_e64 s[10:11], 0, v163
	v_cndmask_b32_e32 v161, v161, v165, vcc
	v_cmp_class_f32_e32 vcc, v157, v156
	v_cndmask_b32_e64 v160, v160, v169, s[10:11]
	v_cmp_lt_f32_e64 s[10:11], 0, v164
	v_mul_f32_e32 v163, 0x37800000, v162
	v_cndmask_b32_e32 v157, v161, v157, vcc
	v_cndmask_b32_e64 v160, v160, v170, s[10:11]
	v_cndmask_b32_e64 v161, v162, v163, s[6:7]
	v_cmp_class_f32_e32 vcc, v159, v156
	v_mul_f32_e32 v162, 0x37800000, v160
	v_div_scale_f32 v163, s[6:7], v157, v157, 1.0
	v_cndmask_b32_e32 v159, v161, v159, vcc
	v_cndmask_b32_e64 v160, v160, v162, s[8:9]
	v_cmp_class_f32_e32 vcc, v158, v156
	v_rcp_f32_e32 v161, v163
	v_div_scale_f32 v162, s[8:9], v159, v159, 1.0
	v_cndmask_b32_e32 v160, v160, v158, vcc
	v_rcp_f32_e32 v166, v162
	v_div_scale_f32 v167, s[10:11], v160, v160, 1.0
	v_rcp_f32_e32 v169, v167
	v_fma_f32 v158, -v163, v161, 1.0
	v_div_scale_f32 v164, s[6:7], 1.0, v157, 1.0
	v_fmac_f32_e32 v161, v158, v161
	v_fma_f32 v158, -v162, v166, 1.0
	v_mul_f32_e32 v170, v164, v161
	v_div_scale_f32 v165, s[8:9], 1.0, v159, 1.0
	v_fmac_f32_e32 v166, v158, v166
	v_fma_f32 v158, -v167, v169, 1.0
	v_fma_f32 v171, -v163, v170, v164
	v_div_scale_f32 v168, s[10:11], 1.0, v160, 1.0
	v_mul_f32_e32 v172, v165, v166
	v_fmac_f32_e32 v169, v158, v169
	v_fmac_f32_e32 v170, v171, v161
	v_fma_f32 v158, -v162, v172, v165
	v_mul_f32_e32 v171, v168, v169
	v_fma_f32 v163, -v163, v170, v164
	s_mov_b64 vcc, s[6:7]
	v_fmac_f32_e32 v172, v158, v166
	v_fma_f32 v158, -v167, v171, v168
	v_div_fmas_f32 v161, v163, v161, v170
	v_fma_f32 v162, -v162, v172, v165
	v_fmac_f32_e32 v171, v158, v169
	v_div_fixup_f32 v158, v161, v157, 1.0
	s_mov_b64 vcc, s[8:9]
	v_div_fmas_f32 v157, v162, v166, v172
	v_fma_f32 v161, -v167, v171, v168
	v_pk_mul_f32 v[80:81], v[80:81], v[158:159] op_sel_hi:[1,0]
	v_pk_mul_f32 v[78:79], v[78:79], v[158:159] op_sel_hi:[1,0]
	s_mov_b64 vcc, s[10:11]
	v_pk_add_f32 v[88:89], v[88:89], 1.0 op_sel_hi:[1,0]
	v_pk_add_f32 v[86:87], v[86:87], 1.0 op_sel_hi:[1,0]
	v_pk_mul_f32 v[76:77], v[76:77], v[158:159] op_sel_hi:[1,0]
	v_pk_mul_f32 v[74:75], v[74:75], v[158:159] op_sel_hi:[1,0]
	v_pk_mul_f32 v[72:73], v[72:73], v[158:159] op_sel_hi:[1,0]
	v_pk_mul_f32 v[70:71], v[70:71], v[158:159] op_sel_hi:[1,0]
	v_pk_mul_f32 v[68:69], v[68:69], v[158:159] op_sel_hi:[1,0]
	v_pk_mul_f32 v[66:67], v[66:67], v[158:159] op_sel_hi:[1,0]
	v_div_fixup_f32 v158, v157, v159, 1.0
	v_div_fmas_f32 v157, v161, v169, v171
	v_pk_mul_f32 v[78:79], v[78:79], v[2:3]
	v_pk_mul_f32 v[80:81], v[80:81], v[4:5]
	v_pk_mul_f32 v[64:65], v[64:65], v[158:159] op_sel_hi:[1,0]
	v_pk_mul_f32 v[62:63], v[62:63], v[158:159] op_sel_hi:[1,0]
	v_pk_mul_f32 v[60:61], v[60:61], v[158:159] op_sel_hi:[1,0]
	v_pk_mul_f32 v[58:59], v[58:59], v[158:159] op_sel_hi:[1,0]
	v_pk_mul_f32 v[56:57], v[56:57], v[158:159] op_sel_hi:[1,0]
	v_pk_mul_f32 v[54:55], v[54:55], v[158:159] op_sel_hi:[1,0]
	v_pk_mul_f32 v[52:53], v[52:53], v[158:159] op_sel_hi:[1,0]
	v_pk_mul_f32 v[158:159], v[50:51], v[158:159] op_sel_hi:[1,0]
	v_div_fixup_f32 v50, v157, v160, 1.0
	v_pk_fma_f32 v[80:81], v[80:81], v[88:89], v[84:85]
	v_pk_fma_f32 v[78:79], v[78:79], v[86:87], v[82:83]
	v_pk_mul_f32 v[86:87], v[52:53], v[16:17]
	v_pk_mul_f32 v[48:49], v[48:49], v[50:51] op_sel_hi:[1,0]
	v_pk_mul_f32 v[46:47], v[46:47], v[50:51] op_sel_hi:[1,0]
	v_bfe_u32 v51, v78, 16, 1
	v_bfe_u32 v53, v80, 16, 1
	v_pk_mul_f32 v[82:83], v[54:55], v[10:11]
	v_pk_mul_f32 v[84:85], v[158:159], v[14:15]
	v_bfe_u32 v52, v79, 16, 1
	v_bfe_u32 v54, v81, 16, 1
	v_pk_mul_f32 v[88:89], v[46:47], v[2:3]
	v_pk_mul_f32 v[158:159], v[48:49], v[4:5]
	v_add3_u32 v46, v78, v51, s5
	v_add3_u32 v48, v80, v53, s5
	v_add3_u32 v47, v79, v52, s5
	v_add3_u32 v49, v81, v54, s5
	v_lshrrev_b32_e32 v46, 16, v46
	v_lshrrev_b32_e32 v48, 16, v48
	v_and_or_b32 v46, v47, s23, v46
	v_and_or_b32 v47, v49, s23, v48
	global_store_dwordx2 v[102:103], v[46:47], off
	global_load_dwordx4 v[46:49], v[138:139], off
	s_nop 0
	global_load_dwordx4 v[52:55], v[124:125], off offset:1024
	v_pk_mul_f32 v[74:75], v[74:75], v[6:7]
	v_pk_mul_f32 v[76:77], v[76:77], v[8:9]
	v_pk_mul_f32 v[70:71], v[70:71], v[10:11]
	v_pk_mul_f32 v[72:73], v[72:73], v[12:13]
	v_pk_mul_f32 v[66:67], v[66:67], v[14:15]
	v_pk_mul_f32 v[68:69], v[68:69], v[16:17]
	v_pk_mul_f32 v[62:63], v[62:63], v[2:3]
	v_pk_mul_f32 v[64:65], v[64:65], v[4:5]
	v_pk_mul_f32 v[58:59], v[58:59], v[6:7]
	v_pk_mul_f32 v[60:61], v[60:61], v[8:9]
	v_pk_mul_f32 v[56:57], v[56:57], v[12:13]
	v_mul_f32_e32 v180, v23, v23
	v_mul_f32_e32 v186, v25, v25
	v_mul_f32_e32 v197, v18, v18
	v_mul_f32_e32 v198, v19, v19
	v_mul_f32_e32 v199, v20, v20
	v_mul_f32_e32 v200, v21, v21
	v_pk_fma_f32 v[144:145], v[22:23], v[22:23], v[180:181] op_sel_hi:[1,1,0]
	v_pk_fma_f32 v[146:147], v[24:25], v[24:25], v[186:187] op_sel_hi:[1,1,0]
	v_mov_b32_e32 v145, v199
	v_mov_b32_e32 v147, v200
	s_mov_b32 s8, s26
	s_waitcnt vmcnt(0) lgkmcnt(0)
	v_pk_add_f32 v[48:49], v[48:49], 1.0 op_sel_hi:[1,0]
	v_pk_add_f32 v[46:47], v[46:47], 1.0 op_sel_hi:[1,0]
	v_pk_fma_f32 v[48:49], v[76:77], v[48:49], v[54:55]
	v_pk_fma_f32 v[46:47], v[74:75], v[46:47], v[52:53]
	v_bfe_u32 v53, v48, 16, 1
	v_bfe_u32 v51, v46, 16, 1
	v_bfe_u32 v52, v47, 16, 1
	v_bfe_u32 v54, v49, 16, 1
	v_add3_u32 v46, v46, v51, s5
	v_add3_u32 v48, v48, v53, s5
	v_add3_u32 v47, v47, v52, s5
	v_add3_u32 v49, v49, v54, s5
	v_lshrrev_b32_e32 v46, 16, v46
	v_lshrrev_b32_e32 v48, 16, v48
	v_and_or_b32 v46, v47, s23, v46
	v_and_or_b32 v47, v49, s23, v48
	global_store_dwordx2 v[102:103], v[46:47], off offset:512
	global_load_dwordx4 v[46:49], v[134:135], off
	s_nop 0
	global_load_dwordx4 v[52:55], v[124:125], off offset:2048
	s_waitcnt vmcnt(0) lgkmcnt(0)
	v_pk_add_f32 v[48:49], v[48:49], 1.0 op_sel_hi:[1,0]
	v_pk_add_f32 v[46:47], v[46:47], 1.0 op_sel_hi:[1,0]
	v_pk_fma_f32 v[48:49], v[72:73], v[48:49], v[54:55]
	v_pk_fma_f32 v[46:47], v[70:71], v[46:47], v[52:53]
	v_bfe_u32 v53, v48, 16, 1
	v_bfe_u32 v51, v46, 16, 1
	v_bfe_u32 v52, v47, 16, 1
	v_bfe_u32 v54, v49, 16, 1
	v_add3_u32 v46, v46, v51, s5
	v_add3_u32 v48, v48, v53, s5
	v_add3_u32 v47, v47, v52, s5
	v_add3_u32 v49, v49, v54, s5
	v_lshrrev_b32_e32 v46, 16, v46
	v_lshrrev_b32_e32 v48, 16, v48
	v_and_or_b32 v46, v47, s23, v46
	v_and_or_b32 v47, v49, s23, v48
	global_store_dwordx2 v[102:103], v[46:47], off offset:1024
	global_load_dwordx4 v[46:49], v[128:129], off
	s_nop 0
	global_load_dwordx4 v[52:55], v[124:125], off offset:3072
	s_waitcnt vmcnt(0) lgkmcnt(0)
	v_pk_add_f32 v[48:49], v[48:49], 1.0 op_sel_hi:[1,0]
	v_pk_add_f32 v[46:47], v[46:47], 1.0 op_sel_hi:[1,0]
	v_pk_fma_f32 v[48:49], v[68:69], v[48:49], v[54:55]
	v_pk_fma_f32 v[46:47], v[66:67], v[46:47], v[52:53]
	v_bfe_u32 v53, v48, 16, 1
	v_bfe_u32 v51, v46, 16, 1
	v_bfe_u32 v52, v47, 16, 1
	v_bfe_u32 v54, v49, 16, 1
	v_add3_u32 v46, v46, v51, s5
	v_add3_u32 v48, v48, v53, s5
	v_add3_u32 v47, v47, v52, s5
	v_add3_u32 v49, v49, v54, s5
	v_lshrrev_b32_e32 v46, 16, v46
	v_lshrrev_b32_e32 v48, 16, v48
	v_and_or_b32 v46, v47, s23, v46
	v_and_or_b32 v47, v49, s23, v48
	global_store_dwordx2 v[102:103], v[46:47], off offset:1536
	global_load_dwordx4 v[46:49], v[126:127], off
	s_nop 0
	global_load_dwordx4 v[52:55], v[110:111], off
	s_waitcnt vmcnt(0) lgkmcnt(0)
	v_pk_add_f32 v[48:49], v[48:49], 1.0 op_sel_hi:[1,0]
	v_pk_add_f32 v[46:47], v[46:47], 1.0 op_sel_hi:[1,0]
	v_pk_fma_f32 v[48:49], v[64:65], v[48:49], v[54:55]
	v_pk_fma_f32 v[46:47], v[62:63], v[46:47], v[52:53]
	v_bfe_u32 v53, v48, 16, 1
	v_bfe_u32 v51, v46, 16, 1
	v_bfe_u32 v52, v47, 16, 1
	v_bfe_u32 v54, v49, 16, 1
	v_add3_u32 v46, v46, v51, s5
	v_add3_u32 v48, v48, v53, s5
	v_add3_u32 v47, v47, v52, s5
	v_add3_u32 v49, v49, v54, s5
	v_lshrrev_b32_e32 v46, 16, v46
	v_lshrrev_b32_e32 v48, 16, v48
	v_and_or_b32 v46, v47, s23, v46
	v_and_or_b32 v47, v49, s23, v48
	global_store_dwordx2 v[102:103], v[46:47], off offset:2048
	global_load_dwordx4 v[46:49], v[120:121], off
	s_nop 0
	global_load_dwordx4 v[52:55], v[110:111], off offset:1024
	s_waitcnt vmcnt(0) lgkmcnt(0)
	v_pk_add_f32 v[48:49], v[48:49], 1.0 op_sel_hi:[1,0]
	v_pk_add_f32 v[46:47], v[46:47], 1.0 op_sel_hi:[1,0]
	v_pk_fma_f32 v[48:49], v[60:61], v[48:49], v[54:55]
	v_pk_fma_f32 v[46:47], v[58:59], v[46:47], v[52:53]
	v_bfe_u32 v53, v48, 16, 1
	v_bfe_u32 v51, v46, 16, 1
	v_bfe_u32 v52, v47, 16, 1
	v_bfe_u32 v54, v49, 16, 1
	v_add3_u32 v46, v46, v51, s5
	v_add3_u32 v48, v48, v53, s5
	v_add3_u32 v47, v47, v52, s5
	v_add3_u32 v49, v49, v54, s5
	v_lshrrev_b32_e32 v46, 16, v46
	v_lshrrev_b32_e32 v48, 16, v48
	v_and_or_b32 v46, v47, s23, v46
	v_and_or_b32 v47, v49, s23, v48
	global_store_dwordx2 v[102:103], v[46:47], off offset:2560
	global_load_dwordx4 v[46:49], v[116:117], off
	s_nop 0
	global_load_dwordx4 v[52:55], v[110:111], off offset:2048
	v_pk_add_f32 v[58:59], v[150:151], v[150:151] op_sel:[0,1] op_sel_hi:[1,0]
	v_pk_add_f32 v[60:61], v[144:145], v[146:147]
	v_mov_b32_e32 v59, v198
	s_waitcnt vmcnt(0) lgkmcnt(0)
	v_pk_add_f32 v[48:49], v[48:49], 1.0 op_sel_hi:[1,0]
	v_pk_add_f32 v[46:47], v[46:47], 1.0 op_sel_hi:[1,0]
	v_pk_fma_f32 v[48:49], v[56:57], v[48:49], v[54:55]
	v_pk_fma_f32 v[46:47], v[82:83], v[46:47], v[52:53]
	v_bfe_u32 v53, v48, 16, 1
	v_bfe_u32 v51, v46, 16, 1
	v_bfe_u32 v52, v47, 16, 1
	v_bfe_u32 v54, v49, 16, 1
	v_add3_u32 v46, v46, v51, s5
	v_add3_u32 v48, v48, v53, s5
	v_add3_u32 v47, v47, v52, s5
	v_add3_u32 v49, v49, v54, s5
	v_lshrrev_b32_e32 v46, 16, v46
	v_lshrrev_b32_e32 v48, 16, v48
	v_and_or_b32 v46, v47, s23, v46
	v_and_or_b32 v47, v49, s23, v48
	global_store_dwordx2 v[102:103], v[46:47], off offset:3072
	global_load_dwordx4 v[46:49], v[112:113], off
	s_nop 0
	global_load_dwordx4 v[52:55], v[110:111], off offset:3072
	v_pk_add_f32 v[56:57], v[148:149], v[148:149] op_sel:[0,1] op_sel_hi:[1,0]
	s_waitcnt vmcnt(0) lgkmcnt(0)
	v_pk_add_f32 v[48:49], v[48:49], 1.0 op_sel_hi:[1,0]
	v_pk_add_f32 v[46:47], v[46:47], 1.0 op_sel_hi:[1,0]
	v_pk_fma_f32 v[48:49], v[86:87], v[48:49], v[54:55]
	v_pk_fma_f32 v[46:47], v[84:85], v[46:47], v[52:53]
	v_bfe_u32 v53, v48, 16, 1
	v_bfe_u32 v51, v46, 16, 1
	v_bfe_u32 v52, v47, 16, 1
	v_bfe_u32 v54, v49, 16, 1
	v_add3_u32 v46, v46, v51, s5
	v_add3_u32 v48, v48, v53, s5
	v_add3_u32 v47, v47, v52, s5
	v_add3_u32 v49, v49, v54, s5
	v_lshrrev_b32_e32 v46, 16, v46
	v_lshrrev_b32_e32 v48, 16, v48
	v_and_or_b32 v46, v47, s23, v46
	v_and_or_b32 v47, v49, s23, v48
	global_store_dwordx2 v[102:103], v[46:47], off offset:3584
	global_load_dwordx4 v[46:49], v[142:143], off
	s_nop 0
	global_load_dwordx4 v[52:55], v[108:109], off
	v_mov_b32_e32 v57, v197
	s_waitcnt vmcnt(0) lgkmcnt(0)
	v_pk_add_f32 v[48:49], v[48:49], 1.0 op_sel_hi:[1,0]
	v_pk_add_f32 v[46:47], v[46:47], 1.0 op_sel_hi:[1,0]
	v_pk_fma_f32 v[48:49], v[158:159], v[48:49], v[54:55]
	v_pk_fma_f32 v[46:47], v[88:89], v[46:47], v[52:53]
	v_bfe_u32 v53, v48, 16, 1
	v_bfe_u32 v51, v46, 16, 1
	v_bfe_u32 v52, v47, 16, 1
	v_bfe_u32 v54, v49, 16, 1
	v_add3_u32 v46, v46, v51, s5
	v_add3_u32 v48, v48, v53, s5
	v_add3_u32 v47, v47, v52, s5
	v_add3_u32 v49, v49, v54, s5
	v_lshrrev_b32_e32 v46, 16, v46
	v_lshrrev_b32_e32 v48, 16, v48
	v_and_or_b32 v46, v47, s23, v46
	v_and_or_b32 v47, v49, s23, v48
	global_store_dwordx2 v[104:105], v[46:47], off
	global_load_dwordx4 v[46:49], v[140:141], off
	s_nop 0
	global_load_dwordx4 v[52:55], v[108:109], off offset:1024
	v_pk_mul_f32 v[44:45], v[44:45], v[50:51] op_sel_hi:[1,0]
	v_pk_mul_f32 v[42:43], v[42:43], v[50:51] op_sel_hi:[1,0]
	v_pk_mul_f32 v[44:45], v[44:45], v[8:9]
	v_pk_mul_f32 v[42:43], v[42:43], v[6:7]
	s_waitcnt vmcnt(0) lgkmcnt(0)
	v_pk_add_f32 v[48:49], v[48:49], 1.0 op_sel_hi:[1,0]
	v_pk_add_f32 v[46:47], v[46:47], 1.0 op_sel_hi:[1,0]
	v_pk_fma_f32 v[44:45], v[44:45], v[48:49], v[54:55]
	v_pk_fma_f32 v[42:43], v[42:43], v[46:47], v[52:53]
	v_bfe_u32 v48, v44, 16, 1
	v_bfe_u32 v46, v42, 16, 1
	v_bfe_u32 v47, v43, 16, 1
	v_bfe_u32 v49, v45, 16, 1
	v_add3_u32 v42, v42, v46, s5
	v_add3_u32 v44, v44, v48, s5
	v_add3_u32 v43, v43, v47, s5
	v_add3_u32 v45, v45, v49, s5
	v_lshrrev_b32_e32 v42, 16, v42
	v_lshrrev_b32_e32 v44, 16, v44
	v_and_or_b32 v42, v43, s23, v42
	v_and_or_b32 v43, v45, s23, v44
	global_store_dwordx2 v[104:105], v[42:43], off offset:512
	global_load_dwordx4 v[42:45], v[136:137], off
	s_nop 0
	global_load_dwordx4 v[46:49], v[108:109], off offset:2048
	v_pk_add_f32 v[52:53], v[56:57], v[58:59]
	s_waitcnt vmcnt(0) lgkmcnt(0)
	v_pk_add_f32 v[44:45], v[44:45], 1.0 op_sel_hi:[1,0]
	v_pk_add_f32 v[52:53], v[52:53], v[60:61]
	v_pk_add_f32 v[42:43], v[42:43], 1.0 op_sel_hi:[1,0]
	v_add_f32_e32 v51, v52, v53
	ds_bpermute_b32 v52, v1, v51
	s_waitcnt lgkmcnt(0)
	v_add_f32_e32 v51, v51, v52
	ds_bpermute_b32 v52, v131, v51
	s_waitcnt lgkmcnt(0)
	v_add_f32_e32 v51, v51, v52
	v_pk_mul_f32 v[40:41], v[40:41], v[50:51] op_sel_hi:[1,0]
	v_pk_mul_f32 v[38:39], v[38:39], v[50:51] op_sel_hi:[1,0]
	v_pk_mul_f32 v[40:41], v[40:41], v[12:13]
	v_pk_mul_f32 v[38:39], v[38:39], v[10:11]
	v_pk_fma_f32 v[40:41], v[40:41], v[44:45], v[48:49]
	v_pk_fma_f32 v[38:39], v[38:39], v[42:43], v[46:47]
	v_bfe_u32 v44, v40, 16, 1
	v_bfe_u32 v42, v38, 16, 1
	v_bfe_u32 v43, v39, 16, 1
	v_bfe_u32 v45, v41, 16, 1
	v_add3_u32 v38, v38, v42, s5
	v_add3_u32 v40, v40, v44, s5
	v_add3_u32 v39, v39, v43, s5
	v_add3_u32 v41, v41, v45, s5
	v_lshrrev_b32_e32 v38, 16, v38
	v_lshrrev_b32_e32 v40, 16, v40
	v_and_or_b32 v38, v39, s23, v38
	v_and_or_b32 v39, v41, s23, v40
	global_store_dwordx2 v[104:105], v[38:39], off offset:1024
	global_load_dwordx4 v[38:41], v[122:123], off
	s_nop 0
	global_load_dwordx4 v[42:45], v[108:109], off offset:3072
	v_pk_mul_f32 v[36:37], v[36:37], v[50:51] op_sel_hi:[1,0]
	v_pk_mul_f32 v[34:35], v[34:35], v[50:51] op_sel_hi:[1,0]
	v_pk_mul_f32 v[36:37], v[36:37], v[16:17]
	v_pk_mul_f32 v[34:35], v[34:35], v[14:15]
	ds_bpermute_b32 v46, v133, v51
	s_waitcnt lgkmcnt(0)
	v_add_f32_e32 v46, v51, v46
	ds_bpermute_b32 v47, v152, v46
	s_waitcnt lgkmcnt(0)
	v_add_f32_e32 v46, v46, v47
	ds_bpermute_b32 v47, v153, v46
	s_waitcnt lgkmcnt(0)
	v_add_f32_e32 v46, v46, v47
	ds_bpermute_b32 v47, v154, v46
	s_waitcnt lgkmcnt(0)
	v_add_f32_e32 v46, v46, v47
	v_fmamk_f32 v46, v46, 0x3a800000, v155
	v_mul_f32_e32 v47, 0x4f800000, v46
	v_cmp_gt_f32_e32 vcc, s4, v46
	s_waitcnt vmcnt(0)
	v_pk_add_f32 v[40:41], v[40:41], 1.0 op_sel_hi:[1,0]
	v_pk_add_f32 v[38:39], v[38:39], 1.0 op_sel_hi:[1,0]
	v_pk_fma_f32 v[36:37], v[36:37], v[40:41], v[44:45]
	v_pk_fma_f32 v[34:35], v[34:35], v[38:39], v[42:43]
	v_bfe_u32 v40, v36, 16, 1
	v_bfe_u32 v38, v34, 16, 1
	v_bfe_u32 v39, v35, 16, 1
	v_bfe_u32 v41, v37, 16, 1
	v_add3_u32 v34, v34, v38, s5
	v_add3_u32 v36, v36, v40, s5
	v_add3_u32 v35, v35, v39, s5
	v_add3_u32 v37, v37, v41, s5
	v_lshrrev_b32_e32 v34, 16, v34
	v_lshrrev_b32_e32 v36, 16, v36
	v_and_or_b32 v34, v35, s23, v34
	v_and_or_b32 v35, v37, s23, v36
	global_store_dwordx2 v[104:105], v[34:35], off offset:1536
	global_load_dwordx4 v[34:37], v[118:119], off
	s_nop 0
	global_load_dwordx4 v[38:41], v[106:107], off
	v_cndmask_b32_e32 v42, v46, v47, vcc
	v_sqrt_f32_e32 v43, v42
	s_waitcnt vmcnt(0) lgkmcnt(0)
	v_pk_add_f32 v[36:37], v[36:37], 1.0 op_sel_hi:[1,0]
	v_add_u32_e32 v44, -1, v43
	v_add_u32_e32 v45, 1, v43
	v_fma_f32 v46, -v44, v43, v42
	v_fma_f32 v47, -v45, v43, v42
	v_cmp_ge_f32_e64 s[6:7], 0, v46
	v_pk_add_f32 v[34:35], v[34:35], 1.0 op_sel_hi:[1,0]
	s_nop 0
	v_cndmask_b32_e64 v43, v43, v44, s[6:7]
	v_cmp_lt_f32_e64 s[6:7], 0, v47
	s_nop 1
	v_cndmask_b32_e64 v43, v43, v45, s[6:7]
	v_mul_f32_e32 v44, 0x37800000, v43
	v_cndmask_b32_e32 v43, v43, v44, vcc
	v_cmp_class_f32_e32 vcc, v42, v156
	s_nop 1
	v_cndmask_b32_e32 v42, v43, v42, vcc
	v_div_scale_f32 v43, s[6:7], v42, v42, 1.0
	v_rcp_f32_e32 v45, v43
	v_div_scale_f32 v44, vcc, 1.0, v42, 1.0
	v_fma_f32 v46, -v43, v45, 1.0
	v_fmac_f32_e32 v45, v46, v45
	v_mul_f32_e32 v46, v44, v45
	v_fma_f32 v47, -v43, v46, v44
	v_fmac_f32_e32 v46, v47, v45
	v_fma_f32 v43, -v43, v46, v44
	v_div_fmas_f32 v43, v43, v45, v46
	v_div_fixup_f32 v42, v43, v42, 1.0
	v_pk_mul_f32 v[32:33], v[32:33], v[42:43] op_sel_hi:[1,0]
	v_pk_mul_f32 v[30:31], v[30:31], v[42:43] op_sel_hi:[1,0]
	v_pk_mul_f32 v[32:33], v[32:33], v[4:5]
	v_pk_mul_f32 v[30:31], v[30:31], v[2:3]
	v_pk_fma_f32 v[32:33], v[32:33], v[36:37], v[40:41]
	v_pk_fma_f32 v[30:31], v[30:31], v[34:35], v[38:39]
	v_bfe_u32 v36, v32, 16, 1
	v_bfe_u32 v34, v30, 16, 1
	v_bfe_u32 v35, v31, 16, 1
	v_bfe_u32 v37, v33, 16, 1
	v_add3_u32 v30, v30, v34, s5
	v_add3_u32 v32, v32, v36, s5
	v_add3_u32 v31, v31, v35, s5
	v_add3_u32 v33, v33, v37, s5
	v_lshrrev_b32_e32 v30, 16, v30
	v_lshrrev_b32_e32 v32, 16, v32
	v_and_or_b32 v30, v31, s23, v30
	v_and_or_b32 v31, v33, s23, v32
	global_store_dwordx2 v[104:105], v[30:31], off offset:2048
	global_load_dwordx4 v[30:33], v[114:115], off
	s_nop 0
	global_load_dwordx4 v[34:37], v[106:107], off offset:1024
	v_pk_mul_f32 v[28:29], v[28:29], v[42:43] op_sel_hi:[1,0]
	v_pk_mul_f32 v[26:27], v[26:27], v[42:43] op_sel_hi:[1,0]
	v_pk_mul_f32 v[28:29], v[28:29], v[8:9]
	v_pk_mul_f32 v[26:27], v[26:27], v[6:7]
	v_lshl_add_u64 v[38:39], s[20:21], 0, v[98:99]
	v_pk_mul_f32 v[24:25], v[24:25], v[42:43] op_sel_hi:[1,0]
	v_pk_mul_f32 v[22:23], v[22:23], v[42:43] op_sel_hi:[1,0]
	v_pk_mul_f32 v[24:25], v[24:25], v[12:13]
	v_pk_mul_f32 v[22:23], v[22:23], v[10:11]
	v_pk_mul_f32 v[20:21], v[20:21], v[42:43] op_sel_hi:[1,0]
	v_pk_mul_f32 v[18:19], v[18:19], v[42:43] op_sel_hi:[1,0]
	v_pk_mul_f32 v[20:21], v[20:21], v[16:17]
	v_pk_mul_f32 v[18:19], v[18:19], v[14:15]
	s_waitcnt vmcnt(0) lgkmcnt(0)
	v_pk_add_f32 v[32:33], v[32:33], 1.0 op_sel_hi:[1,0]
	v_pk_add_f32 v[30:31], v[30:31], 1.0 op_sel_hi:[1,0]
	v_pk_fma_f32 v[28:29], v[28:29], v[32:33], v[36:37]
	v_pk_fma_f32 v[26:27], v[26:27], v[30:31], v[34:35]
	v_bfe_u32 v32, v28, 16, 1
	v_bfe_u32 v30, v26, 16, 1
	v_bfe_u32 v31, v27, 16, 1
	v_bfe_u32 v33, v29, 16, 1
	v_add3_u32 v26, v26, v30, s5
	v_add3_u32 v28, v28, v32, s5
	v_add3_u32 v27, v27, v31, s5
	v_add3_u32 v29, v29, v33, s5
	v_lshrrev_b32_e32 v26, 16, v26
	v_lshrrev_b32_e32 v28, 16, v28
	v_and_or_b32 v26, v27, s23, v26
	v_and_or_b32 v27, v29, s23, v28
	global_store_dwordx2 v[104:105], v[26:27], off offset:2560
	global_load_dwordx4 v[26:29], v[38:39], off
	s_nop 0
	global_load_dwordx4 v[30:33], v[106:107], off offset:2048
	v_lshl_add_u64 v[34:35], s[20:21], 0, v[100:101]
	s_waitcnt vmcnt(0) lgkmcnt(0)
	v_pk_add_f32 v[28:29], v[28:29], 1.0 op_sel_hi:[1,0]
	v_pk_add_f32 v[26:27], v[26:27], 1.0 op_sel_hi:[1,0]
	v_pk_fma_f32 v[24:25], v[24:25], v[28:29], v[32:33]
	v_pk_fma_f32 v[22:23], v[22:23], v[26:27], v[30:31]
	v_bfe_u32 v28, v24, 16, 1
	v_bfe_u32 v26, v22, 16, 1
	v_bfe_u32 v27, v23, 16, 1
	v_bfe_u32 v29, v25, 16, 1
	v_add3_u32 v22, v22, v26, s5
	v_add3_u32 v24, v24, v28, s5
	v_add3_u32 v23, v23, v27, s5
	v_add3_u32 v25, v25, v29, s5
	v_lshrrev_b32_e32 v22, 16, v22
	v_lshrrev_b32_e32 v24, 16, v24
	v_and_or_b32 v22, v23, s23, v22
	v_and_or_b32 v23, v25, s23, v24
	global_store_dwordx2 v[104:105], v[22:23], off offset:3072
	global_load_dwordx4 v[22:25], v[34:35], off
	s_nop 0
	global_load_dwordx4 v[26:29], v[106:107], off offset:3072
	s_waitcnt vmcnt(0) lgkmcnt(0)
	v_pk_add_f32 v[24:25], v[24:25], 1.0 op_sel_hi:[1,0]
	v_pk_add_f32 v[22:23], v[22:23], 1.0 op_sel_hi:[1,0]
	v_pk_fma_f32 v[20:21], v[20:21], v[24:25], v[28:29]
	v_pk_fma_f32 v[18:19], v[18:19], v[22:23], v[26:27]
	v_bfe_u32 v24, v20, 16, 1
	v_bfe_u32 v22, v18, 16, 1
	v_bfe_u32 v23, v19, 16, 1
	v_bfe_u32 v25, v21, 16, 1
	v_add3_u32 v18, v18, v22, s5
	v_add3_u32 v20, v20, v24, s5
	v_add3_u32 v19, v19, v23, s5
	v_add3_u32 v21, v21, v25, s5
	v_lshrrev_b32_e32 v18, 16, v18
	v_lshrrev_b32_e32 v20, 16, v20
	v_and_or_b32 v18, v19, s23, v18
	v_and_or_b32 v19, v21, s23, v20
	global_store_dwordx2 v[104:105], v[18:19], off offset:3584
	s_cbranch_scc1 .LBB0_1004

.LBB0_1075:
	s_and_b64 vcc, exec, s[6:7]
	s_cbranch_vccz .LBB0_1527
	s_lshl_b32 s14, s14, 8
	v_add_u32_e32 v138, s14, v133
	v_mov_b64_e32 v[146:147], s[22:23]
	v_mad_i64_i32 v[148:149], s[6:7], v138, s82, v[146:147]
	s_lshl_b32 s10, s10, 8
	s_lshl_b64 s[6:7], s[10:11], 2
	v_lshl_add_u64 v[148:149], v[148:149], 0, s[6:7]
	v_mov_b32_e32 v145, v139
	v_lshl_add_u64 v[148:149], v[148:149], 0, v[144:145]
	global_store_dwordx4 v[148:149], v[126:129], off
	global_store_dwordx4 v[148:149], v[122:125], off offset:64
	global_store_dwordx4 v[148:149], v[106:109], off offset:512
	global_store_dwordx4 v[148:149], v[98:101], off offset:576
	s_nop 1
	v_add_u32_e32 v98, s14, v170
	v_mad_i64_i32 v[98:99], s[8:9], v98, s82, v[146:147]
	v_lshl_add_u64 v[98:99], v[98:99], 0, s[6:7]
	v_lshl_add_u64 v[98:99], v[98:99], 0, v[144:145]
	global_store_dwordx4 v[98:99], v[118:121], off
	global_store_dwordx4 v[98:99], v[114:117], off offset:64
	global_store_dwordx4 v[98:99], v[90:93], off offset:512
	global_store_dwordx4 v[98:99], v[82:85], off offset:576
	s_nop 1
	v_add_u32_e32 v82, s14, v171
	v_mad_i64_i32 v[82:83], s[8:9], v82, s82, v[146:147]
	v_lshl_add_u64 v[82:83], v[82:83], 0, s[6:7]
	v_lshl_add_u64 v[82:83], v[82:83], 0, v[144:145]
	global_store_dwordx4 v[82:83], v[110:113], off
	global_store_dwordx4 v[82:83], v[102:105], off offset:64
	global_store_dwordx4 v[82:83], v[78:81], off offset:512
	global_store_dwordx4 v[82:83], v[74:77], off offset:576
	s_nop 1
	v_add_u32_e32 v74, s14, v172
	v_mad_i64_i32 v[74:75], s[8:9], v74, s82, v[146:147]
	v_lshl_add_u64 v[74:75], v[74:75], 0, s[6:7]
	v_lshl_add_u64 v[74:75], v[74:75], 0, v[144:145]
	global_store_dwordx4 v[74:75], v[94:97], off
	global_store_dwordx4 v[74:75], v[86:89], off offset:64
	global_store_dwordx4 v[74:75], v[70:73], off offset:512
	global_store_dwordx4 v[74:75], v[66:69], off offset:576
	s_nop 1
	v_add_u32_e32 v66, 0x80, v138
	v_mad_i64_i32 v[66:67], s[8:9], v66, s82, v[146:147]
	v_lshl_add_u64 v[66:67], v[66:67], 0, s[6:7]
	v_lshl_add_u64 v[66:67], v[66:67], 0, v[144:145]
	global_store_dwordx4 v[66:67], v[62:65], off
	global_store_dwordx4 v[66:67], v[58:61], off offset:64
	global_store_dwordx4 v[66:67], v[42:45], off offset:512
	global_store_dwordx4 v[66:67], v[34:37], off offset:576
	s_nop 1
	v_add_u32_e32 v34, 0x90, v138
	v_mad_i64_i32 v[34:35], s[8:9], v34, s82, v[146:147]
	v_lshl_add_u64 v[34:35], v[34:35], 0, s[6:7]
	v_lshl_add_u64 v[34:35], v[34:35], 0, v[144:145]
	global_store_dwordx4 v[34:35], v[54:57], off
	global_store_dwordx4 v[34:35], v[50:53], off offset:64
	global_store_dwordx4 v[34:35], v[26:29], off offset:512
	global_store_dwordx4 v[34:35], v[18:21], off offset:576
	s_nop 1
	v_add_u32_e32 v18, 0xa0, v138
	v_mad_i64_i32 v[18:19], s[8:9], v18, s82, v[146:147]
	v_lshl_add_u64 v[18:19], v[18:19], 0, s[6:7]
	v_lshl_add_u64 v[18:19], v[18:19], 0, v[144:145]
	global_store_dwordx4 v[18:19], v[46:49], off
	global_store_dwordx4 v[18:19], v[38:41], off offset:64
	global_store_dwordx4 v[18:19], v[14:17], off offset:512
	global_store_dwordx4 v[18:19], v[10:13], off offset:576
	s_nop 1
	v_add_u32_e32 v10, 0xb0, v138
	v_mad_i64_i32 v[10:11], s[8:9], v10, s82, v[146:147]
	v_lshl_add_u64 v[10:11], v[10:11], 0, s[6:7]
	v_lshl_add_u64 v[10:11], v[10:11], 0, v[144:145]
	global_store_dwordx4 v[10:11], v[30:33], off
	global_store_dwordx4 v[10:11], v[22:25], off offset:64
	global_store_dwordx4 v[10:11], v[6:9], off offset:512
	global_store_dwordx4 v[10:11], v[2:5], off offset:576
	s_andn2_b64 vcc, exec, s[62:63]
	s_mov_b64 s[6:7], -1
	s_cbranch_vccnz .LBB0_1068
	s_branch .LBB0_1528

.LBB0_1078:
	v_mov_b32_e32 v138, v1
	v_mov_b32_e32 v145, v131
	s_lshl_b32 s6, s14, 8
	s_add_i32 s6, s6, s71
	v_add_u32_e32 v154, s6, v138
	v_lshlrev_b32_e32 v138, 6, v138
	v_lshl_add_u32 v146, v145, 2, s72
	v_and_b32_e32 v145, 0x3c0, v138
	v_ashrrev_i32_e32 v138, 10, v154
	v_ashrrev_i32_e32 v155, 31, v154
	v_and_b32_e32 v168, -2, v138
	v_lshrrev_b32_e32 v138, 3, v154
	s_cmp_gt_i32 s10, 1
	v_lshlrev_b64 v[158:159], 9, v[154:155]
	v_lshlrev_b64 v[156:157], 10, v[154:155]
	v_and_b32_e32 v155, 0xfe, v138
	v_and_b32_e32 v138, 0x1fff, v154
	s_cselect_b64 s[68:69], -1, 0
	v_cmp_lt_u32_e64 s[8:9], s79, v138
	v_add_u32_e32 v138, 0xffffe200, v138
	v_ashrrev_i32_e32 v160, 13, v154
	v_lshlrev_b64 v[162:163], 10, v[138:139]
	s_mov_b64 s[6:7], -1
	s_and_b64 vcc, exec, s[68:69]
	s_cbranch_vccz .LBB0_1090
	v_bfe_u32 v138, v126, 16, 1
	v_add3_u32 v138, v126, v138, s80
	v_bfe_u32 v147, v127, 16, 1
	v_lshrrev_b32_e32 v138, 16, v138
	v_add3_u32 v147, v127, v147, s80
	v_and_or_b32 v148, v147, s81, v138
	v_bfe_u32 v138, v128, 16, 1
	v_add3_u32 v138, v128, v138, s80
	v_bfe_u32 v147, v129, 16, 1
	v_lshrrev_b32_e32 v138, 16, v138
	v_add3_u32 v147, v129, v147, s80
	v_and_or_b32 v149, v147, s81, v138
	s_cmp_lt_i32 s10, 3
	s_cbranch_scc1 .LBB0_1087
	s_cmp_lg_u32 s10, 3
	s_cbranch_scc0 .LBB0_1084
	v_lshlrev_b32_e32 v152, 1, v146
	v_lshl_add_u64 v[150:151], s[50:51], 0, v[158:159]
	v_ashrrev_i32_e32 v153, 31, v152
	v_lshl_add_u64 v[150:151], v[150:151], 0, v[152:153]
	global_store_dwordx2 v[150:151], v[148:149], off
	s_and_saveexec_b64 s[6:7], s[8:9]
	s_cbranch_execz .LBB0_1083
	v_ashrrev_i32_e32 v161, 31, v160
	v_lshlrev_b64 v[150:151], 19, v[160:161]
	v_lshl_add_u64 v[150:151], s[52:53], 0, v[150:151]
	v_lshl_add_u64 v[150:151], v[150:151], 0, v[162:163]
	v_ashrrev_i32_e32 v147, 31, v146
	v_lshl_add_u64 v[150:151], v[146:147], 2, v[150:151]
	global_store_dwordx4 v[150:151], v[126:129], off

.LBB0_1084:
	s_andn2_b64 vcc, exec, s[6:7]
	s_cbranch_vccnz .LBB0_1086
	v_lshlrev_b32_e32 v152, 1, v146
	v_lshl_add_u64 v[150:151], s[24:25], 0, v[158:159]
	v_ashrrev_i32_e32 v153, 31, v152
	v_lshl_add_u64 v[150:151], v[150:151], 0, v[152:153]
	global_store_dwordx2 v[150:151], v[148:149], off
	v_lshl_add_u64 v[150:151], s[44:45], 0, v[156:157]
	v_ashrrev_i32_e32 v147, 31, v146
	v_lshl_add_u64 v[150:151], v[146:147], 2, v[150:151]
	global_store_dwordx4 v[150:151], v[126:129], off

.LBB0_1087:
	s_andn2_b64 vcc, exec, s[6:7]
	s_cbranch_vccnz .LBB0_1089
	v_ashrrev_i32_e32 v138, 7, v146
	v_add_u32_e32 v150, v138, v168
	v_ashrrev_i32_e32 v151, 31, v150
	v_lshrrev_b32_e32 v147, 6, v146
	v_lshlrev_b64 v[150:151], 8, v[150:151]
	v_and_or_b32 v138, v147, 1, v150
	v_or_b32_e32 v150, v138, v155
	v_lshlrev_b64 v[150:151], 10, v[150:151]
	v_and_or_b32 v138, v146, 60, v150
	v_or_b32_e32 v150, v138, v145
	v_lshl_add_u64 v[150:151], v[150:151], 1, s[46:47]
	global_store_dwordx2 v[150:151], v[148:149], off
	v_lshl_add_u64 v[148:149], s[48:49], 0, v[156:157]
	v_ashrrev_i32_e32 v147, 31, v146
	v_lshl_add_u64 v[148:149], v[146:147], 2, v[148:149]
	global_store_dwordx4 v[148:149], v[126:129], off

.LBB0_1090:
	s_lshl_b32 s26, s10, 8
	v_add_u32_e32 v148, s26, v146
	s_and_b64 vcc, exec, s[6:7]
	v_lshl_add_u64 v[164:165], s[54:55], 0, v[156:157]
	v_ashrrev_i32_e32 v149, 31, v148
	s_cbranch_vccz .LBB0_1092
	v_pk_mul_f32 v[152:153], v[126:127], s[56:57] op_sel_hi:[1,0]
	v_pk_mul_f32 v[150:151], v[128:129], s[56:57] op_sel_hi:[1,0]
	v_bfe_u32 v138, v152, 16, 1
	v_add3_u32 v138, v152, v138, s80
	v_bfe_u32 v147, v153, 16, 1
	v_lshrrev_b32_e32 v138, 16, v138
	v_add3_u32 v147, v153, v147, s80
	v_and_or_b32 v152, v147, s81, v138
	v_bfe_u32 v138, v150, 16, 1
	v_add3_u32 v138, v150, v138, s80
	v_bfe_u32 v147, v151, 16, 1
	v_lshrrev_b32_e32 v138, 16, v138
	v_add3_u32 v147, v151, v147, s80
	v_and_or_b32 v153, v147, s81, v138
	v_lshl_add_u64 v[150:151], v[148:149], 1, v[164:165]
	global_store_dwordx2 v[150:151], v[152:153], off
.LBB0_1092:
	v_cndmask_b32_e64 v138, 0, 1, s[68:69]
	v_add_u32_e32 v178, 16, v146
	v_cmp_ne_u32_e64 s[6:7], 1, v138
	s_andn2_b64 vcc, exec, s[68:69]
	s_mov_b64 s[68:69], -1
	s_cbranch_vccnz .LBB0_1128
	v_bfe_u32 v138, v122, 16, 1
	v_add3_u32 v138, v122, v138, s80
	v_bfe_u32 v147, v123, 16, 1
	v_lshrrev_b32_e32 v138, 16, v138
	v_add3_u32 v147, v123, v147, s80
	v_and_or_b32 v150, v147, s81, v138
	v_bfe_u32 v138, v124, 16, 1
	v_add3_u32 v138, v124, v138, s80
	v_bfe_u32 v147, v125, 16, 1
	v_lshrrev_b32_e32 v138, 16, v138
	v_add3_u32 v147, v125, v147, s80
	v_and_or_b32 v151, v147, s81, v138
	s_cmp_lt_i32 s10, 3
	s_cbranch_scc1 .LBB0_1101
	s_cmp_lg_u32 s10, 3
	s_cbranch_scc0 .LBB0_1098
	v_lshlrev_b32_e32 v166, 1, v178
	v_lshl_add_u64 v[152:153], s[50:51], 0, v[158:159]
	v_ashrrev_i32_e32 v167, 31, v166
	v_lshl_add_u64 v[152:153], v[152:153], 0, v[166:167]
	global_store_dwordx2 v[152:153], v[150:151], off
	s_and_saveexec_b64 s[68:69], s[8:9]
	s_cbranch_execz .LBB0_1097
	v_ashrrev_i32_e32 v161, 31, v160
	v_lshlrev_b64 v[152:153], 19, v[160:161]
	v_lshl_add_u64 v[152:153], s[52:53], 0, v[152:153]
	v_lshl_add_u64 v[152:153], v[152:153], 0, v[162:163]
	v_ashrrev_i32_e32 v147, 31, v146
	v_lshl_add_u64 v[152:153], v[146:147], 2, v[152:153]
	global_store_dwordx4 v[152:153], v[122:125], off offset:64

.LBB0_1098:
	s_andn2_b64 vcc, exec, s[68:69]
	s_cbranch_vccnz .LBB0_1100
	v_lshlrev_b32_e32 v166, 1, v178
	v_lshl_add_u64 v[152:153], s[24:25], 0, v[158:159]
	v_ashrrev_i32_e32 v167, 31, v166
	v_lshl_add_u64 v[152:153], v[152:153], 0, v[166:167]
	global_store_dwordx2 v[152:153], v[150:151], off
	v_lshl_add_u64 v[152:153], s[44:45], 0, v[156:157]
	v_ashrrev_i32_e32 v147, 31, v146
	v_lshl_add_u64 v[152:153], v[146:147], 2, v[152:153]
	global_store_dwordx4 v[152:153], v[122:125], off offset:64

.LBB0_1101:
	s_andn2_b64 vcc, exec, s[68:69]
	s_cbranch_vccnz .LBB0_1103
	v_ashrrev_i32_e32 v138, 7, v178
	v_add_u32_e32 v152, v138, v168
	v_ashrrev_i32_e32 v153, 31, v152
	v_lshrrev_b32_e32 v147, 6, v178
	v_lshlrev_b64 v[152:153], 8, v[152:153]
	v_and_or_b32 v138, v147, 1, v152
	v_or_b32_e32 v152, v138, v155
	v_lshlrev_b64 v[152:153], 10, v[152:153]
	v_and_or_b32 v138, v178, 60, v152
	v_or_b32_e32 v152, v138, v145
	v_lshl_add_u64 v[152:153], v[152:153], 1, s[46:47]
	global_store_dwordx2 v[152:153], v[150:151], off
	v_lshl_add_u64 v[150:151], s[48:49], 0, v[156:157]
	v_ashrrev_i32_e32 v147, 31, v146
	v_lshl_add_u64 v[150:151], v[146:147], 2, v[150:151]
	global_store_dwordx4 v[150:151], v[122:125], off offset:64

.LBB0_1105:
	v_bfe_u32 v138, v106, 16, 1
	v_add3_u32 v138, v106, v138, s80
	v_bfe_u32 v147, v107, 16, 1
	v_lshrrev_b32_e32 v138, 16, v138
	v_add3_u32 v147, v107, v147, s80
	v_and_or_b32 v152, v147, s81, v138
	v_bfe_u32 v138, v108, 16, 1
	v_add3_u32 v138, v108, v138, s80
	v_bfe_u32 v147, v109, 16, 1
	v_lshrrev_b32_e32 v138, 16, v138
	v_add3_u32 v147, v109, v147, s80
	v_and_or_b32 v153, v147, s81, v138
	s_cmp_lt_i32 s10, 3
	s_cbranch_scc1 .LBB0_1113
	s_cmp_lg_u32 s10, 3
	s_cbranch_scc0 .LBB0_1110
	v_lshlrev_b32_e32 v182, 1, v180
	v_lshl_add_u64 v[166:167], s[50:51], 0, v[158:159]
	v_ashrrev_i32_e32 v183, 31, v182
	v_lshl_add_u64 v[166:167], v[166:167], 0, v[182:183]
	global_store_dwordx2 v[166:167], v[152:153], off
	s_and_saveexec_b64 s[68:69], s[8:9]
	s_cbranch_execz .LBB0_1109
	v_ashrrev_i32_e32 v161, 31, v160
	v_lshlrev_b64 v[166:167], 19, v[160:161]
	v_lshl_add_u64 v[166:167], s[52:53], 0, v[166:167]
	v_lshl_add_u64 v[166:167], v[166:167], 0, v[162:163]
	v_ashrrev_i32_e32 v147, 31, v146
	v_lshl_add_u64 v[166:167], v[146:147], 2, v[166:167]
	global_store_dwordx4 v[166:167], v[106:109], off offset:512

.LBB0_1110:
	s_andn2_b64 vcc, exec, s[68:69]
	s_cbranch_vccnz .LBB0_1112
	v_lshlrev_b32_e32 v182, 1, v180
	v_lshl_add_u64 v[166:167], s[24:25], 0, v[158:159]
	v_ashrrev_i32_e32 v183, 31, v182
	v_lshl_add_u64 v[166:167], v[166:167], 0, v[182:183]
	global_store_dwordx2 v[166:167], v[152:153], off
	v_lshl_add_u64 v[166:167], s[44:45], 0, v[156:157]
	v_ashrrev_i32_e32 v147, 31, v146
	v_lshl_add_u64 v[166:167], v[146:147], 2, v[166:167]
	global_store_dwordx4 v[166:167], v[106:109], off offset:512

.LBB0_1113:
	s_andn2_b64 vcc, exec, s[68:69]
	s_cbranch_vccnz .LBB0_1115
	v_ashrrev_i32_e32 v138, 7, v180
	v_add_u32_e32 v166, v138, v168
	v_ashrrev_i32_e32 v167, 31, v166
	v_lshrrev_b32_e32 v147, 6, v146
	v_lshlrev_b64 v[166:167], 8, v[166:167]
	v_and_or_b32 v138, v147, 1, v166
	v_or_b32_e32 v166, v138, v155
	v_lshlrev_b64 v[166:167], 10, v[166:167]
	v_and_or_b32 v138, v146, 60, v166
	v_or_b32_e32 v166, v138, v145
	v_lshl_add_u64 v[166:167], v[166:167], 1, s[46:47]
	global_store_dwordx2 v[166:167], v[152:153], off
	v_lshl_add_u64 v[152:153], s[48:49], 0, v[156:157]
	v_ashrrev_i32_e32 v147, 31, v146
	v_lshl_add_u64 v[152:153], v[146:147], 2, v[152:153]
	global_store_dwordx4 v[152:153], v[106:109], off offset:512

.LBB0_1117:
	v_bfe_u32 v138, v98, 16, 1
	v_add3_u32 v138, v98, v138, s80
	v_bfe_u32 v147, v99, 16, 1
	v_lshrrev_b32_e32 v138, 16, v138
	v_add3_u32 v147, v99, v147, s80
	v_and_or_b32 v166, v147, s81, v138
	v_bfe_u32 v138, v100, 16, 1
	v_add3_u32 v138, v100, v138, s80
	v_bfe_u32 v147, v101, 16, 1
	v_lshrrev_b32_e32 v138, 16, v138
	v_add3_u32 v147, v101, v147, s80
	v_and_or_b32 v167, v147, s81, v138
	s_cmp_lt_i32 s10, 3
	s_cbranch_scc1 .LBB0_1125
	s_cmp_lg_u32 s10, 3
	s_cbranch_scc0 .LBB0_1122
	v_lshlrev_b32_e32 v184, 1, v179
	v_lshl_add_u64 v[182:183], s[50:51], 0, v[158:159]
	v_ashrrev_i32_e32 v185, 31, v184
	v_lshl_add_u64 v[182:183], v[182:183], 0, v[184:185]
	global_store_dwordx2 v[182:183], v[166:167], off
	s_and_saveexec_b64 s[68:69], s[8:9]
	s_cbranch_execz .LBB0_1121
	v_ashrrev_i32_e32 v161, 31, v160
	v_lshlrev_b64 v[160:161], 19, v[160:161]
	v_lshl_add_u64 v[160:161], s[52:53], 0, v[160:161]
	v_lshl_add_u64 v[160:161], v[160:161], 0, v[162:163]
	v_ashrrev_i32_e32 v147, 31, v146
	v_lshl_add_u64 v[160:161], v[146:147], 2, v[160:161]
	global_store_dwordx4 v[160:161], v[98:101], off offset:576

.LBB0_1122:
	s_andn2_b64 vcc, exec, s[68:69]
	s_cbranch_vccnz .LBB0_1124
	v_lshlrev_b32_e32 v160, 1, v179
	v_lshl_add_u64 v[158:159], s[24:25], 0, v[158:159]
	v_ashrrev_i32_e32 v161, 31, v160
	v_lshl_add_u64 v[158:159], v[158:159], 0, v[160:161]
	global_store_dwordx2 v[158:159], v[166:167], off
	v_lshl_add_u64 v[158:159], s[44:45], 0, v[156:157]
	v_ashrrev_i32_e32 v147, 31, v146
	v_lshl_add_u64 v[158:159], v[146:147], 2, v[158:159]
	global_store_dwordx4 v[158:159], v[98:101], off offset:576

.LBB0_1125:
	s_andn2_b64 vcc, exec, s[68:69]
	s_cbranch_vccnz .LBB0_1127
	v_ashrrev_i32_e32 v138, 7, v179
	v_add_u32_e32 v158, v138, v168
	v_ashrrev_i32_e32 v159, 31, v158
	v_lshrrev_b32_e32 v147, 6, v179
	v_lshlrev_b64 v[158:159], 8, v[158:159]
	v_and_or_b32 v138, v147, 1, v158
	v_or_b32_e32 v158, v138, v155
	v_lshlrev_b64 v[158:159], 10, v[158:159]
	v_and_or_b32 v138, v179, 60, v158
	v_or_b32_e32 v158, v138, v145
	v_lshl_add_u64 v[156:157], s[48:49], 0, v[156:157]
	v_ashrrev_i32_e32 v147, 31, v146
	v_lshl_add_u64 v[158:159], v[158:159], 1, s[46:47]
	v_lshl_add_u64 v[156:157], v[146:147], 2, v[156:157]
	global_store_dwordx2 v[158:159], v[166:167], off
	global_store_dwordx4 v[156:157], v[98:101], off offset:576

.LBB0_1128:
	v_add_u32_e32 v150, s26, v178
	s_and_b64 vcc, exec, s[68:69]
	v_ashrrev_i32_e32 v151, 31, v150
	s_cbranch_vccz .LBB0_1104
	v_pk_mul_f32 v[166:167], v[122:123], s[56:57] op_sel_hi:[1,0]
	v_pk_mul_f32 v[152:153], v[124:125], s[56:57] op_sel_hi:[1,0]
	v_bfe_u32 v138, v166, 16, 1
	v_add3_u32 v138, v166, v138, s80
	v_bfe_u32 v147, v167, 16, 1
	v_lshrrev_b32_e32 v138, 16, v138
	v_add3_u32 v147, v167, v147, s80
	v_and_or_b32 v166, v147, s81, v138
	v_bfe_u32 v138, v152, 16, 1
	v_add3_u32 v138, v152, v138, s80
	v_bfe_u32 v147, v153, 16, 1
	v_lshrrev_b32_e32 v138, 16, v138
	v_add3_u32 v147, v153, v147, s80
	v_and_or_b32 v167, v147, s81, v138
	v_lshl_add_u64 v[152:153], v[150:151], 1, v[164:165]
	global_store_dwordx2 v[152:153], v[166:167], off
	v_add_u32_e32 v180, 0x80, v146
	s_and_b64 vcc, exec, s[6:7]
	s_mov_b64 s[68:69], -1
	s_cbranch_vccz .LBB0_1105
.LBB0_1130:
	v_add_u32_e32 v152, s26, v180
	s_and_b64 vcc, exec, s[68:69]
	v_ashrrev_i32_e32 v153, 31, v152
	s_cbranch_vccz .LBB0_1116
	v_pk_mul_f32 v[182:183], v[106:107], s[56:57] op_sel_hi:[1,0]
	v_pk_mul_f32 v[166:167], v[108:109], s[56:57] op_sel_hi:[1,0]
	v_bfe_u32 v138, v182, 16, 1
	v_add3_u32 v138, v182, v138, s80
	v_bfe_u32 v147, v183, 16, 1
	v_lshrrev_b32_e32 v138, 16, v138
	v_add3_u32 v147, v183, v147, s80
	v_and_or_b32 v182, v147, s81, v138
	v_bfe_u32 v138, v166, 16, 1
	v_add3_u32 v138, v166, v138, s80
	v_bfe_u32 v147, v167, 16, 1
	v_lshrrev_b32_e32 v138, 16, v138
	v_add3_u32 v147, v167, v147, s80
	v_and_or_b32 v183, v147, s81, v138
	v_lshl_add_u64 v[166:167], v[152:153], 1, v[164:165]
	global_store_dwordx2 v[166:167], v[182:183], off
	v_add_u32_e32 v179, 0x90, v146
	s_and_b64 vcc, exec, s[6:7]
	s_mov_b64 s[68:69], -1
	s_cbranch_vccz .LBB0_1117
.LBB0_1132:
	v_add_u32_e32 v156, s26, v179
	s_and_b64 vcc, exec, s[68:69]
	v_ashrrev_i32_e32 v157, 31, v156
	s_cbranch_vccz .LBB0_1134
	v_pk_mul_f32 v[160:161], v[98:99], s[56:57] op_sel_hi:[1,0]
	v_pk_mul_f32 v[158:159], v[100:101], s[56:57] op_sel_hi:[1,0]
	v_bfe_u32 v138, v160, 16, 1
	v_add3_u32 v138, v160, v138, s80
	v_bfe_u32 v147, v161, 16, 1
	v_lshrrev_b32_e32 v138, 16, v138
	v_add3_u32 v147, v161, v147, s80
	v_and_or_b32 v160, v147, s81, v138
	v_bfe_u32 v138, v158, 16, 1
	v_add3_u32 v138, v158, v138, s80
	v_bfe_u32 v147, v159, 16, 1
	v_lshrrev_b32_e32 v138, 16, v138
	v_add3_u32 v147, v159, v147, s80
	v_and_or_b32 v161, v147, s81, v138
	v_lshl_add_u64 v[158:159], v[156:157], 1, v[164:165]
	global_store_dwordx2 v[158:159], v[160:161], off
.LBB0_1134:
	v_add_u32_e32 v162, 16, v154
	v_ashrrev_i32_e32 v138, 10, v162
	v_and_b32_e32 v181, -2, v138
	v_lshrrev_b32_e32 v138, 3, v162
	v_and_b32_e32 v155, 0xfe, v138
	v_and_b32_e32 v138, 0x1fff, v162
	v_ashrrev_i32_e32 v163, 31, v162
	v_cmp_lt_u32_e64 s[8:9], s79, v138
	v_add_u32_e32 v138, 0xffffe200, v138
	v_lshlrev_b64 v[160:161], 9, v[162:163]
	v_lshlrev_b64 v[158:159], 10, v[162:163]
	v_ashrrev_i32_e32 v162, 13, v162
	v_lshlrev_b64 v[164:165], 10, v[138:139]
	s_and_b64 vcc, exec, s[6:7]
	s_mov_b64 s[68:69], -1
	s_cbranch_vccnz .LBB0_1182
	v_bfe_u32 v138, v118, 16, 1
	v_add3_u32 v138, v118, v138, s80
	v_bfe_u32 v147, v119, 16, 1
	v_lshrrev_b32_e32 v138, 16, v138
	v_add3_u32 v147, v119, v147, s80
	v_and_or_b32 v166, v147, s81, v138
	v_bfe_u32 v138, v120, 16, 1
	v_add3_u32 v138, v120, v138, s80
	v_bfe_u32 v147, v121, 16, 1
	v_lshrrev_b32_e32 v138, 16, v138
	v_add3_u32 v147, v121, v147, s80
	v_and_or_b32 v167, v147, s81, v138
	s_cmp_lt_i32 s10, 3
	s_cbranch_scc1 .LBB0_1143
	s_cmp_lg_u32 s10, 3
	s_cbranch_scc0 .LBB0_1140
	v_lshlrev_b32_e32 v182, 1, v146
	v_lshl_add_u64 v[168:169], s[50:51], 0, v[160:161]
	v_ashrrev_i32_e32 v183, 31, v182
	v_lshl_add_u64 v[168:169], v[168:169], 0, v[182:183]
	global_store_dwordx2 v[168:169], v[166:167], off
	s_and_saveexec_b64 s[68:69], s[8:9]
	s_cbranch_execz .LBB0_1139
	v_ashrrev_i32_e32 v163, 31, v162
	v_lshlrev_b64 v[168:169], 19, v[162:163]
	v_lshl_add_u64 v[168:169], s[52:53], 0, v[168:169]
	v_lshl_add_u64 v[168:169], v[168:169], 0, v[164:165]
	v_ashrrev_i32_e32 v147, 31, v146
	v_lshl_add_u64 v[168:169], v[146:147], 2, v[168:169]
	global_store_dwordx4 v[168:169], v[118:121], off

.LBB0_1140:
	s_andn2_b64 vcc, exec, s[68:69]
	s_cbranch_vccnz .LBB0_1142
	v_lshlrev_b32_e32 v182, 1, v146
	v_lshl_add_u64 v[168:169], s[24:25], 0, v[160:161]
	v_ashrrev_i32_e32 v183, 31, v182
	v_lshl_add_u64 v[168:169], v[168:169], 0, v[182:183]
	global_store_dwordx2 v[168:169], v[166:167], off
	v_lshl_add_u64 v[168:169], s[44:45], 0, v[158:159]
	v_ashrrev_i32_e32 v147, 31, v146
	v_lshl_add_u64 v[168:169], v[146:147], 2, v[168:169]
	global_store_dwordx4 v[168:169], v[118:121], off

.LBB0_1143:
	s_andn2_b64 vcc, exec, s[68:69]
	s_cbranch_vccnz .LBB0_1145
	v_ashrrev_i32_e32 v138, 7, v146
	v_add_u32_e32 v168, v181, v138
	v_ashrrev_i32_e32 v169, 31, v168
	v_lshrrev_b32_e32 v147, 6, v146
	v_lshlrev_b64 v[168:169], 8, v[168:169]
	v_and_or_b32 v138, v147, 1, v168
	v_or_b32_e32 v168, v138, v155
	v_lshlrev_b64 v[168:169], 10, v[168:169]
	v_and_or_b32 v138, v146, 60, v168
	v_or_b32_e32 v168, v138, v145
	v_lshl_add_u64 v[168:169], v[168:169], 1, s[46:47]
	global_store_dwordx2 v[168:169], v[166:167], off
	v_lshl_add_u64 v[166:167], s[48:49], 0, v[158:159]
	v_ashrrev_i32_e32 v147, 31, v146
	v_lshl_add_u64 v[166:167], v[146:147], 2, v[166:167]
	global_store_dwordx4 v[166:167], v[118:121], off

.LBB0_1147:
	v_bfe_u32 v138, v114, 16, 1
	v_add3_u32 v138, v114, v138, s80
	v_bfe_u32 v147, v115, 16, 1
	v_lshrrev_b32_e32 v138, 16, v138
	v_add3_u32 v147, v115, v147, s80
	v_and_or_b32 v168, v147, s81, v138
	v_bfe_u32 v138, v116, 16, 1
	v_add3_u32 v138, v116, v138, s80
	v_bfe_u32 v147, v117, 16, 1
	v_lshrrev_b32_e32 v138, 16, v138
	v_add3_u32 v147, v117, v147, s80
	v_and_or_b32 v169, v147, s81, v138
	s_cmp_lt_i32 s10, 3
	s_cbranch_scc1 .LBB0_1155
	s_cmp_lg_u32 s10, 3
	s_cbranch_scc0 .LBB0_1152
	v_lshlrev_b32_e32 v184, 1, v178
	v_lshl_add_u64 v[182:183], s[50:51], 0, v[160:161]
	v_ashrrev_i32_e32 v185, 31, v184
	v_lshl_add_u64 v[182:183], v[182:183], 0, v[184:185]
	global_store_dwordx2 v[182:183], v[168:169], off
	s_and_saveexec_b64 s[68:69], s[8:9]
	s_cbranch_execz .LBB0_1151
	v_ashrrev_i32_e32 v163, 31, v162
	v_lshlrev_b64 v[182:183], 19, v[162:163]
	v_lshl_add_u64 v[182:183], s[52:53], 0, v[182:183]
	v_lshl_add_u64 v[182:183], v[182:183], 0, v[164:165]
	v_ashrrev_i32_e32 v147, 31, v146
	v_lshl_add_u64 v[182:183], v[146:147], 2, v[182:183]
	global_store_dwordx4 v[182:183], v[114:117], off offset:64

.LBB0_1152:
	s_andn2_b64 vcc, exec, s[68:69]
	s_cbranch_vccnz .LBB0_1154
	v_lshlrev_b32_e32 v184, 1, v178
	v_lshl_add_u64 v[182:183], s[24:25], 0, v[160:161]
	v_ashrrev_i32_e32 v185, 31, v184
	v_lshl_add_u64 v[182:183], v[182:183], 0, v[184:185]
	global_store_dwordx2 v[182:183], v[168:169], off
	v_lshl_add_u64 v[182:183], s[44:45], 0, v[158:159]
	v_ashrrev_i32_e32 v147, 31, v146
	v_lshl_add_u64 v[182:183], v[146:147], 2, v[182:183]
	global_store_dwordx4 v[182:183], v[114:117], off offset:64

.LBB0_1155:
	s_andn2_b64 vcc, exec, s[68:69]
	s_cbranch_vccnz .LBB0_1157
	v_ashrrev_i32_e32 v138, 7, v178
	v_add_u32_e32 v182, v138, v181
	v_ashrrev_i32_e32 v183, 31, v182
	v_lshrrev_b32_e32 v147, 6, v178
	v_lshlrev_b64 v[182:183], 8, v[182:183]
	v_and_or_b32 v138, v147, 1, v182
	v_or_b32_e32 v182, v138, v155
	v_lshlrev_b64 v[182:183], 10, v[182:183]
	v_and_or_b32 v138, v178, 60, v182
	v_or_b32_e32 v182, v138, v145
	v_lshl_add_u64 v[182:183], v[182:183], 1, s[46:47]
	global_store_dwordx2 v[182:183], v[168:169], off
	v_lshl_add_u64 v[168:169], s[48:49], 0, v[158:159]
	v_ashrrev_i32_e32 v147, 31, v146
	v_lshl_add_u64 v[168:169], v[146:147], 2, v[168:169]
	global_store_dwordx4 v[168:169], v[114:117], off offset:64

.LBB0_1159:
	v_bfe_u32 v138, v90, 16, 1
	v_add3_u32 v138, v90, v138, s80
	v_bfe_u32 v147, v91, 16, 1
	v_lshrrev_b32_e32 v138, 16, v138
	v_add3_u32 v147, v91, v147, s80
	v_and_or_b32 v168, v147, s81, v138
	v_bfe_u32 v138, v92, 16, 1
	v_add3_u32 v138, v92, v138, s80
	v_bfe_u32 v147, v93, 16, 1
	v_lshrrev_b32_e32 v138, 16, v138
	v_add3_u32 v147, v93, v147, s80
	v_and_or_b32 v169, v147, s81, v138
	s_cmp_lt_i32 s10, 3
	s_cbranch_scc1 .LBB0_1167
	s_cmp_lg_u32 s10, 3
	s_cbranch_scc0 .LBB0_1164
	v_lshlrev_b32_e32 v184, 1, v180
	v_lshl_add_u64 v[182:183], s[50:51], 0, v[160:161]
	v_ashrrev_i32_e32 v185, 31, v184
	v_lshl_add_u64 v[182:183], v[182:183], 0, v[184:185]
	global_store_dwordx2 v[182:183], v[168:169], off
	s_and_saveexec_b64 s[68:69], s[8:9]
	s_cbranch_execz .LBB0_1163
	v_ashrrev_i32_e32 v163, 31, v162
	v_lshlrev_b64 v[182:183], 19, v[162:163]
	v_lshl_add_u64 v[182:183], s[52:53], 0, v[182:183]
	v_lshl_add_u64 v[182:183], v[182:183], 0, v[164:165]
	v_ashrrev_i32_e32 v147, 31, v146
	v_lshl_add_u64 v[182:183], v[146:147], 2, v[182:183]
	global_store_dwordx4 v[182:183], v[90:93], off offset:512

.LBB0_1164:
	s_andn2_b64 vcc, exec, s[68:69]
	s_cbranch_vccnz .LBB0_1166
	v_lshlrev_b32_e32 v184, 1, v180
	v_lshl_add_u64 v[182:183], s[24:25], 0, v[160:161]
	v_ashrrev_i32_e32 v185, 31, v184
	v_lshl_add_u64 v[182:183], v[182:183], 0, v[184:185]
	global_store_dwordx2 v[182:183], v[168:169], off
	v_lshl_add_u64 v[182:183], s[44:45], 0, v[158:159]
	v_ashrrev_i32_e32 v147, 31, v146
	v_lshl_add_u64 v[182:183], v[146:147], 2, v[182:183]
	global_store_dwordx4 v[182:183], v[90:93], off offset:512

.LBB0_1167:
	s_andn2_b64 vcc, exec, s[68:69]
	s_cbranch_vccnz .LBB0_1169
	v_ashrrev_i32_e32 v138, 7, v180
	v_add_u32_e32 v182, v138, v181
	v_ashrrev_i32_e32 v183, 31, v182
	v_lshrrev_b32_e32 v147, 6, v146
	v_lshlrev_b64 v[182:183], 8, v[182:183]
	v_and_or_b32 v138, v147, 1, v182
	v_or_b32_e32 v182, v138, v155
	v_lshlrev_b64 v[182:183], 10, v[182:183]
	v_and_or_b32 v138, v146, 60, v182
	v_or_b32_e32 v182, v138, v145
	v_lshl_add_u64 v[182:183], v[182:183], 1, s[46:47]
	global_store_dwordx2 v[182:183], v[168:169], off
	v_lshl_add_u64 v[168:169], s[48:49], 0, v[158:159]
	v_ashrrev_i32_e32 v147, 31, v146
	v_lshl_add_u64 v[168:169], v[146:147], 2, v[168:169]
	global_store_dwordx4 v[168:169], v[90:93], off offset:512

.LBB0_1171:
	v_bfe_u32 v138, v82, 16, 1
	v_add3_u32 v138, v82, v138, s80
	v_bfe_u32 v147, v83, 16, 1
	v_lshrrev_b32_e32 v138, 16, v138
	v_add3_u32 v147, v83, v147, s80
	v_and_or_b32 v168, v147, s81, v138
	v_bfe_u32 v138, v84, 16, 1
	v_add3_u32 v138, v84, v138, s80
	v_bfe_u32 v147, v85, 16, 1
	v_lshrrev_b32_e32 v138, 16, v138
	v_add3_u32 v147, v85, v147, s80
	v_and_or_b32 v169, v147, s81, v138
	s_cmp_lt_i32 s10, 3
	s_cbranch_scc1 .LBB0_1179
	s_cmp_lg_u32 s10, 3
	s_cbranch_scc0 .LBB0_1176
	v_lshlrev_b32_e32 v184, 1, v179
	v_lshl_add_u64 v[182:183], s[50:51], 0, v[160:161]
	v_ashrrev_i32_e32 v185, 31, v184
	v_lshl_add_u64 v[182:183], v[182:183], 0, v[184:185]
	global_store_dwordx2 v[182:183], v[168:169], off
	s_and_saveexec_b64 s[68:69], s[8:9]
	s_cbranch_execz .LBB0_1175
	v_ashrrev_i32_e32 v163, 31, v162
	v_lshlrev_b64 v[162:163], 19, v[162:163]
	v_lshl_add_u64 v[162:163], s[52:53], 0, v[162:163]
	v_lshl_add_u64 v[162:163], v[162:163], 0, v[164:165]
	v_ashrrev_i32_e32 v147, 31, v146
	v_lshl_add_u64 v[162:163], v[146:147], 2, v[162:163]
	global_store_dwordx4 v[162:163], v[82:85], off offset:576

.LBB0_1176:
	s_andn2_b64 vcc, exec, s[68:69]
	s_cbranch_vccnz .LBB0_1178
	v_lshlrev_b32_e32 v162, 1, v179
	v_lshl_add_u64 v[160:161], s[24:25], 0, v[160:161]
	v_ashrrev_i32_e32 v163, 31, v162
	v_lshl_add_u64 v[160:161], v[160:161], 0, v[162:163]
	global_store_dwordx2 v[160:161], v[168:169], off
	v_lshl_add_u64 v[160:161], s[44:45], 0, v[158:159]
	v_ashrrev_i32_e32 v147, 31, v146
	v_lshl_add_u64 v[160:161], v[146:147], 2, v[160:161]
	global_store_dwordx4 v[160:161], v[82:85], off offset:576

.LBB0_1179:
	s_andn2_b64 vcc, exec, s[68:69]
	s_cbranch_vccnz .LBB0_1181
	v_ashrrev_i32_e32 v138, 7, v179
	v_add_u32_e32 v160, v138, v181
	v_ashrrev_i32_e32 v161, 31, v160
	v_lshrrev_b32_e32 v147, 6, v179
	v_lshlrev_b64 v[160:161], 8, v[160:161]
	v_and_or_b32 v138, v147, 1, v160
	v_or_b32_e32 v160, v138, v155
	v_lshlrev_b64 v[160:161], 10, v[160:161]
	v_and_or_b32 v138, v179, 60, v160
	v_or_b32_e32 v160, v138, v145
	v_lshl_add_u64 v[158:159], s[48:49], 0, v[158:159]
	v_ashrrev_i32_e32 v147, 31, v146
	v_lshl_add_u64 v[160:161], v[160:161], 1, s[46:47]
	v_lshl_add_u64 v[158:159], v[146:147], 2, v[158:159]
	global_store_dwordx2 v[160:161], v[168:169], off
	global_store_dwordx4 v[158:159], v[82:85], off offset:576

.LBB0_1182:
	s_and_b64 vcc, exec, s[68:69]
	v_lshl_add_u64 v[166:167], s[54:55], 0, v[158:159]
	s_cbranch_vccz .LBB0_1146
	v_pk_mul_f32 v[182:183], v[118:119], s[56:57] op_sel_hi:[1,0]
	v_pk_mul_f32 v[168:169], v[120:121], s[56:57] op_sel_hi:[1,0]
	v_bfe_u32 v138, v182, 16, 1
	v_add3_u32 v138, v182, v138, s80
	v_bfe_u32 v147, v183, 16, 1
	v_lshrrev_b32_e32 v138, 16, v138
	v_add3_u32 v147, v183, v147, s80
	v_and_or_b32 v182, v147, s81, v138
	v_bfe_u32 v138, v168, 16, 1
	v_add3_u32 v138, v168, v138, s80
	v_bfe_u32 v147, v169, 16, 1
	v_lshrrev_b32_e32 v138, 16, v138
	v_add3_u32 v147, v169, v147, s80
	v_and_or_b32 v183, v147, s81, v138
	v_lshl_add_u64 v[168:169], v[148:149], 1, v[166:167]
	global_store_dwordx2 v[168:169], v[182:183], off
	s_and_b64 vcc, exec, s[6:7]
	s_mov_b64 s[68:69], -1
	s_cbranch_vccz .LBB0_1147
.LBB0_1184:
	s_and_b64 vcc, exec, s[68:69]
	s_cbranch_vccz .LBB0_1158
	v_pk_mul_f32 v[182:183], v[114:115], s[56:57] op_sel_hi:[1,0]
	v_pk_mul_f32 v[168:169], v[116:117], s[56:57] op_sel_hi:[1,0]
	v_bfe_u32 v138, v182, 16, 1
	v_add3_u32 v138, v182, v138, s80
	v_bfe_u32 v147, v183, 16, 1
	v_lshrrev_b32_e32 v138, 16, v138
	v_add3_u32 v147, v183, v147, s80
	v_and_or_b32 v182, v147, s81, v138
	v_bfe_u32 v138, v168, 16, 1
	v_add3_u32 v138, v168, v138, s80
	v_bfe_u32 v147, v169, 16, 1
	v_lshrrev_b32_e32 v138, 16, v138
	v_add3_u32 v147, v169, v147, s80
	v_and_or_b32 v183, v147, s81, v138
	v_lshl_add_u64 v[168:169], v[150:151], 1, v[166:167]
	global_store_dwordx2 v[168:169], v[182:183], off
	s_and_b64 vcc, exec, s[6:7]
	s_mov_b64 s[68:69], -1
	s_cbranch_vccz .LBB0_1159
.LBB0_1186:
	s_and_b64 vcc, exec, s[68:69]
	s_cbranch_vccz .LBB0_1170
	v_pk_mul_f32 v[182:183], v[90:91], s[56:57] op_sel_hi:[1,0]
	v_pk_mul_f32 v[168:169], v[92:93], s[56:57] op_sel_hi:[1,0]
	v_bfe_u32 v138, v182, 16, 1
	v_add3_u32 v138, v182, v138, s80
	v_bfe_u32 v147, v183, 16, 1
	v_lshrrev_b32_e32 v138, 16, v138
	v_add3_u32 v147, v183, v147, s80
	v_and_or_b32 v182, v147, s81, v138
	v_bfe_u32 v138, v168, 16, 1
	v_add3_u32 v138, v168, v138, s80
	v_bfe_u32 v147, v169, 16, 1
	v_lshrrev_b32_e32 v138, 16, v138
	v_add3_u32 v147, v169, v147, s80
	v_and_or_b32 v183, v147, s81, v138
	v_lshl_add_u64 v[168:169], v[152:153], 1, v[166:167]
	global_store_dwordx2 v[168:169], v[182:183], off
	s_and_b64 vcc, exec, s[6:7]
	s_mov_b64 s[68:69], -1
	s_cbranch_vccz .LBB0_1171
.LBB0_1188:
	s_and_b64 vcc, exec, s[68:69]
	s_cbranch_vccz .LBB0_1190
	v_pk_mul_f32 v[160:161], v[82:83], s[56:57] op_sel_hi:[1,0]
	v_pk_mul_f32 v[158:159], v[84:85], s[56:57] op_sel_hi:[1,0]
	v_bfe_u32 v138, v160, 16, 1
	v_add3_u32 v138, v160, v138, s80
	v_bfe_u32 v147, v161, 16, 1
	v_lshrrev_b32_e32 v138, 16, v138
	v_add3_u32 v147, v161, v147, s80
	v_and_or_b32 v160, v147, s81, v138
	v_bfe_u32 v138, v158, 16, 1
	v_add3_u32 v138, v158, v138, s80
	v_bfe_u32 v147, v159, 16, 1
	v_lshrrev_b32_e32 v138, 16, v138
	v_add3_u32 v147, v159, v147, s80
	v_and_or_b32 v161, v147, s81, v138
	v_lshl_add_u64 v[158:159], v[156:157], 1, v[166:167]
	global_store_dwordx2 v[158:159], v[160:161], off
.LBB0_1190:
	v_add_u32_e32 v162, 32, v154
	v_ashrrev_i32_e32 v138, 10, v162
	v_and_b32_e32 v181, -2, v138
	v_lshrrev_b32_e32 v138, 3, v162
	v_and_b32_e32 v155, 0xfe, v138
	v_and_b32_e32 v138, 0x1fff, v162
	v_ashrrev_i32_e32 v163, 31, v162
	v_cmp_lt_u32_e64 s[8:9], s79, v138
	v_add_u32_e32 v138, 0xffffe200, v138
	v_lshlrev_b64 v[160:161], 9, v[162:163]
	v_lshlrev_b64 v[158:159], 10, v[162:163]
	v_ashrrev_i32_e32 v162, 13, v162
	v_lshlrev_b64 v[164:165], 10, v[138:139]
	s_and_b64 vcc, exec, s[6:7]
	s_mov_b64 s[68:69], -1
	s_cbranch_vccnz .LBB0_1238
	v_bfe_u32 v138, v110, 16, 1
	v_add3_u32 v138, v110, v138, s80
	v_bfe_u32 v147, v111, 16, 1
	v_lshrrev_b32_e32 v138, 16, v138
	v_add3_u32 v147, v111, v147, s80
	v_and_or_b32 v166, v147, s81, v138
	v_bfe_u32 v138, v112, 16, 1
	v_add3_u32 v138, v112, v138, s80
	v_bfe_u32 v147, v113, 16, 1
	v_lshrrev_b32_e32 v138, 16, v138
	v_add3_u32 v147, v113, v147, s80
	v_and_or_b32 v167, v147, s81, v138
	s_cmp_lt_i32 s10, 3
	s_cbranch_scc1 .LBB0_1199
	s_cmp_lg_u32 s10, 3
	s_cbranch_scc0 .LBB0_1196
	v_lshlrev_b32_e32 v182, 1, v146
	v_lshl_add_u64 v[168:169], s[50:51], 0, v[160:161]
	v_ashrrev_i32_e32 v183, 31, v182
	v_lshl_add_u64 v[168:169], v[168:169], 0, v[182:183]
	global_store_dwordx2 v[168:169], v[166:167], off
	s_and_saveexec_b64 s[68:69], s[8:9]
	s_cbranch_execz .LBB0_1195
	v_ashrrev_i32_e32 v163, 31, v162
	v_lshlrev_b64 v[168:169], 19, v[162:163]
	v_lshl_add_u64 v[168:169], s[52:53], 0, v[168:169]
	v_lshl_add_u64 v[168:169], v[168:169], 0, v[164:165]
	v_ashrrev_i32_e32 v147, 31, v146
	v_lshl_add_u64 v[168:169], v[146:147], 2, v[168:169]
	global_store_dwordx4 v[168:169], v[110:113], off

.LBB0_1196:
	s_andn2_b64 vcc, exec, s[68:69]
	s_cbranch_vccnz .LBB0_1198
	v_lshlrev_b32_e32 v182, 1, v146
	v_lshl_add_u64 v[168:169], s[24:25], 0, v[160:161]
	v_ashrrev_i32_e32 v183, 31, v182
	v_lshl_add_u64 v[168:169], v[168:169], 0, v[182:183]
	global_store_dwordx2 v[168:169], v[166:167], off
	v_lshl_add_u64 v[168:169], s[44:45], 0, v[158:159]
	v_ashrrev_i32_e32 v147, 31, v146
	v_lshl_add_u64 v[168:169], v[146:147], 2, v[168:169]
	global_store_dwordx4 v[168:169], v[110:113], off

.LBB0_1199:
	s_andn2_b64 vcc, exec, s[68:69]
	s_cbranch_vccnz .LBB0_1201
	v_ashrrev_i32_e32 v138, 7, v146
	v_add_u32_e32 v168, v181, v138
	v_ashrrev_i32_e32 v169, 31, v168
	v_lshrrev_b32_e32 v147, 6, v146
	v_lshlrev_b64 v[168:169], 8, v[168:169]
	v_and_or_b32 v138, v147, 1, v168
	v_or_b32_e32 v168, v138, v155
	v_lshlrev_b64 v[168:169], 10, v[168:169]
	v_and_or_b32 v138, v146, 60, v168
	v_or_b32_e32 v168, v138, v145
	v_lshl_add_u64 v[168:169], v[168:169], 1, s[46:47]
	global_store_dwordx2 v[168:169], v[166:167], off
	v_lshl_add_u64 v[166:167], s[48:49], 0, v[158:159]
	v_ashrrev_i32_e32 v147, 31, v146
	v_lshl_add_u64 v[166:167], v[146:147], 2, v[166:167]
	global_store_dwordx4 v[166:167], v[110:113], off

.LBB0_1203:
	v_bfe_u32 v138, v102, 16, 1
	v_add3_u32 v138, v102, v138, s80
	v_bfe_u32 v147, v103, 16, 1
	v_lshrrev_b32_e32 v138, 16, v138
	v_add3_u32 v147, v103, v147, s80
	v_and_or_b32 v168, v147, s81, v138
	v_bfe_u32 v138, v104, 16, 1
	v_add3_u32 v138, v104, v138, s80
	v_bfe_u32 v147, v105, 16, 1
	v_lshrrev_b32_e32 v138, 16, v138
	v_add3_u32 v147, v105, v147, s80
	v_and_or_b32 v169, v147, s81, v138
	s_cmp_lt_i32 s10, 3
	s_cbranch_scc1 .LBB0_1211
	s_cmp_lg_u32 s10, 3
	s_cbranch_scc0 .LBB0_1208
	v_lshlrev_b32_e32 v184, 1, v178
	v_lshl_add_u64 v[182:183], s[50:51], 0, v[160:161]
	v_ashrrev_i32_e32 v185, 31, v184
	v_lshl_add_u64 v[182:183], v[182:183], 0, v[184:185]
	global_store_dwordx2 v[182:183], v[168:169], off
	s_and_saveexec_b64 s[68:69], s[8:9]
	s_cbranch_execz .LBB0_1207
	v_ashrrev_i32_e32 v163, 31, v162
	v_lshlrev_b64 v[182:183], 19, v[162:163]
	v_lshl_add_u64 v[182:183], s[52:53], 0, v[182:183]
	v_lshl_add_u64 v[182:183], v[182:183], 0, v[164:165]
	v_ashrrev_i32_e32 v147, 31, v146
	v_lshl_add_u64 v[182:183], v[146:147], 2, v[182:183]
	global_store_dwordx4 v[182:183], v[102:105], off offset:64

.LBB0_1208:
	s_andn2_b64 vcc, exec, s[68:69]
	s_cbranch_vccnz .LBB0_1210
	v_lshlrev_b32_e32 v184, 1, v178
	v_lshl_add_u64 v[182:183], s[24:25], 0, v[160:161]
	v_ashrrev_i32_e32 v185, 31, v184
	v_lshl_add_u64 v[182:183], v[182:183], 0, v[184:185]
	global_store_dwordx2 v[182:183], v[168:169], off
	v_lshl_add_u64 v[182:183], s[44:45], 0, v[158:159]
	v_ashrrev_i32_e32 v147, 31, v146
	v_lshl_add_u64 v[182:183], v[146:147], 2, v[182:183]
	global_store_dwordx4 v[182:183], v[102:105], off offset:64

.LBB0_1211:
	s_andn2_b64 vcc, exec, s[68:69]
	s_cbranch_vccnz .LBB0_1213
	v_ashrrev_i32_e32 v138, 7, v178
	v_add_u32_e32 v182, v138, v181
	v_ashrrev_i32_e32 v183, 31, v182
	v_lshrrev_b32_e32 v147, 6, v178
	v_lshlrev_b64 v[182:183], 8, v[182:183]
	v_and_or_b32 v138, v147, 1, v182
	v_or_b32_e32 v182, v138, v155
	v_lshlrev_b64 v[182:183], 10, v[182:183]
	v_and_or_b32 v138, v178, 60, v182
	v_or_b32_e32 v182, v138, v145
	v_lshl_add_u64 v[182:183], v[182:183], 1, s[46:47]
	global_store_dwordx2 v[182:183], v[168:169], off
	v_lshl_add_u64 v[168:169], s[48:49], 0, v[158:159]
	v_ashrrev_i32_e32 v147, 31, v146
	v_lshl_add_u64 v[168:169], v[146:147], 2, v[168:169]
	global_store_dwordx4 v[168:169], v[102:105], off offset:64

.LBB0_1215:
	v_bfe_u32 v138, v78, 16, 1
	v_add3_u32 v138, v78, v138, s80
	v_bfe_u32 v147, v79, 16, 1
	v_lshrrev_b32_e32 v138, 16, v138
	v_add3_u32 v147, v79, v147, s80
	v_and_or_b32 v168, v147, s81, v138
	v_bfe_u32 v138, v80, 16, 1
	v_add3_u32 v138, v80, v138, s80
	v_bfe_u32 v147, v81, 16, 1
	v_lshrrev_b32_e32 v138, 16, v138
	v_add3_u32 v147, v81, v147, s80
	v_and_or_b32 v169, v147, s81, v138
	s_cmp_lt_i32 s10, 3
	s_cbranch_scc1 .LBB0_1223
	s_cmp_lg_u32 s10, 3
	s_cbranch_scc0 .LBB0_1220
	v_lshlrev_b32_e32 v184, 1, v180
	v_lshl_add_u64 v[182:183], s[50:51], 0, v[160:161]
	v_ashrrev_i32_e32 v185, 31, v184
	v_lshl_add_u64 v[182:183], v[182:183], 0, v[184:185]
	global_store_dwordx2 v[182:183], v[168:169], off
	s_and_saveexec_b64 s[68:69], s[8:9]
	s_cbranch_execz .LBB0_1219
	v_ashrrev_i32_e32 v163, 31, v162
	v_lshlrev_b64 v[182:183], 19, v[162:163]
	v_lshl_add_u64 v[182:183], s[52:53], 0, v[182:183]
	v_lshl_add_u64 v[182:183], v[182:183], 0, v[164:165]
	v_ashrrev_i32_e32 v147, 31, v146
	v_lshl_add_u64 v[182:183], v[146:147], 2, v[182:183]
	global_store_dwordx4 v[182:183], v[78:81], off offset:512

.LBB0_1220:
	s_andn2_b64 vcc, exec, s[68:69]
	s_cbranch_vccnz .LBB0_1222
	v_lshlrev_b32_e32 v184, 1, v180
	v_lshl_add_u64 v[182:183], s[24:25], 0, v[160:161]
	v_ashrrev_i32_e32 v185, 31, v184
	v_lshl_add_u64 v[182:183], v[182:183], 0, v[184:185]
	global_store_dwordx2 v[182:183], v[168:169], off
	v_lshl_add_u64 v[182:183], s[44:45], 0, v[158:159]
	v_ashrrev_i32_e32 v147, 31, v146
	v_lshl_add_u64 v[182:183], v[146:147], 2, v[182:183]
	global_store_dwordx4 v[182:183], v[78:81], off offset:512

.LBB0_1223:
	s_andn2_b64 vcc, exec, s[68:69]
	s_cbranch_vccnz .LBB0_1225
	v_ashrrev_i32_e32 v138, 7, v180
	v_add_u32_e32 v182, v138, v181
	v_ashrrev_i32_e32 v183, 31, v182
	v_lshrrev_b32_e32 v147, 6, v146
	v_lshlrev_b64 v[182:183], 8, v[182:183]
	v_and_or_b32 v138, v147, 1, v182
	v_or_b32_e32 v182, v138, v155
	v_lshlrev_b64 v[182:183], 10, v[182:183]
	v_and_or_b32 v138, v146, 60, v182
	v_or_b32_e32 v182, v138, v145
	v_lshl_add_u64 v[182:183], v[182:183], 1, s[46:47]
	global_store_dwordx2 v[182:183], v[168:169], off
	v_lshl_add_u64 v[168:169], s[48:49], 0, v[158:159]
	v_ashrrev_i32_e32 v147, 31, v146
	v_lshl_add_u64 v[168:169], v[146:147], 2, v[168:169]
	global_store_dwordx4 v[168:169], v[78:81], off offset:512

.LBB0_1227:
	v_bfe_u32 v138, v74, 16, 1
	v_add3_u32 v138, v74, v138, s80
	v_bfe_u32 v147, v75, 16, 1
	v_lshrrev_b32_e32 v138, 16, v138
	v_add3_u32 v147, v75, v147, s80
	v_and_or_b32 v168, v147, s81, v138
	v_bfe_u32 v138, v76, 16, 1
	v_add3_u32 v138, v76, v138, s80
	v_bfe_u32 v147, v77, 16, 1
	v_lshrrev_b32_e32 v138, 16, v138
	v_add3_u32 v147, v77, v147, s80
	v_and_or_b32 v169, v147, s81, v138
	s_cmp_lt_i32 s10, 3
	s_cbranch_scc1 .LBB0_1235
	s_cmp_lg_u32 s10, 3
	s_cbranch_scc0 .LBB0_1232
	v_lshlrev_b32_e32 v184, 1, v179
	v_lshl_add_u64 v[182:183], s[50:51], 0, v[160:161]
	v_ashrrev_i32_e32 v185, 31, v184
	v_lshl_add_u64 v[182:183], v[182:183], 0, v[184:185]
	global_store_dwordx2 v[182:183], v[168:169], off
	s_and_saveexec_b64 s[68:69], s[8:9]
	s_cbranch_execz .LBB0_1231
	v_ashrrev_i32_e32 v163, 31, v162
	v_lshlrev_b64 v[162:163], 19, v[162:163]
	v_lshl_add_u64 v[162:163], s[52:53], 0, v[162:163]
	v_lshl_add_u64 v[162:163], v[162:163], 0, v[164:165]
	v_ashrrev_i32_e32 v147, 31, v146
	v_lshl_add_u64 v[162:163], v[146:147], 2, v[162:163]
	global_store_dwordx4 v[162:163], v[74:77], off offset:576

.LBB0_1232:
	s_andn2_b64 vcc, exec, s[68:69]
	s_cbranch_vccnz .LBB0_1234
	v_lshlrev_b32_e32 v162, 1, v179
	v_lshl_add_u64 v[160:161], s[24:25], 0, v[160:161]
	v_ashrrev_i32_e32 v163, 31, v162
	v_lshl_add_u64 v[160:161], v[160:161], 0, v[162:163]
	global_store_dwordx2 v[160:161], v[168:169], off
	v_lshl_add_u64 v[160:161], s[44:45], 0, v[158:159]
	v_ashrrev_i32_e32 v147, 31, v146
	v_lshl_add_u64 v[160:161], v[146:147], 2, v[160:161]
	global_store_dwordx4 v[160:161], v[74:77], off offset:576

.LBB0_1235:
	s_andn2_b64 vcc, exec, s[68:69]
	s_cbranch_vccnz .LBB0_1237
	v_ashrrev_i32_e32 v138, 7, v179
	v_add_u32_e32 v160, v138, v181
	v_ashrrev_i32_e32 v161, 31, v160
	v_lshrrev_b32_e32 v147, 6, v179
	v_lshlrev_b64 v[160:161], 8, v[160:161]
	v_and_or_b32 v138, v147, 1, v160
	v_or_b32_e32 v160, v138, v155
	v_lshlrev_b64 v[160:161], 10, v[160:161]
	v_and_or_b32 v138, v179, 60, v160
	v_or_b32_e32 v160, v138, v145
	v_lshl_add_u64 v[158:159], s[48:49], 0, v[158:159]
	v_ashrrev_i32_e32 v147, 31, v146
	v_lshl_add_u64 v[160:161], v[160:161], 1, s[46:47]
	v_lshl_add_u64 v[158:159], v[146:147], 2, v[158:159]
	global_store_dwordx2 v[160:161], v[168:169], off
	global_store_dwordx4 v[158:159], v[74:77], off offset:576

.LBB0_1238:
	s_and_b64 vcc, exec, s[68:69]
	v_lshl_add_u64 v[166:167], s[54:55], 0, v[158:159]
	s_cbranch_vccz .LBB0_1202
	v_pk_mul_f32 v[182:183], v[110:111], s[56:57] op_sel_hi:[1,0]
	v_pk_mul_f32 v[168:169], v[112:113], s[56:57] op_sel_hi:[1,0]
	v_bfe_u32 v138, v182, 16, 1
	v_add3_u32 v138, v182, v138, s80
	v_bfe_u32 v147, v183, 16, 1
	v_lshrrev_b32_e32 v138, 16, v138
	v_add3_u32 v147, v183, v147, s80
	v_and_or_b32 v182, v147, s81, v138
	v_bfe_u32 v138, v168, 16, 1
	v_add3_u32 v138, v168, v138, s80
	v_bfe_u32 v147, v169, 16, 1
	v_lshrrev_b32_e32 v138, 16, v138
	v_add3_u32 v147, v169, v147, s80
	v_and_or_b32 v183, v147, s81, v138
	v_lshl_add_u64 v[168:169], v[148:149], 1, v[166:167]
	global_store_dwordx2 v[168:169], v[182:183], off
	s_and_b64 vcc, exec, s[6:7]
	s_mov_b64 s[68:69], -1
	s_cbranch_vccz .LBB0_1203
.LBB0_1240:
	s_and_b64 vcc, exec, s[68:69]
	s_cbranch_vccz .LBB0_1214
	v_pk_mul_f32 v[182:183], v[102:103], s[56:57] op_sel_hi:[1,0]
	v_pk_mul_f32 v[168:169], v[104:105], s[56:57] op_sel_hi:[1,0]
	v_bfe_u32 v138, v182, 16, 1
	v_add3_u32 v138, v182, v138, s80
	v_bfe_u32 v147, v183, 16, 1
	v_lshrrev_b32_e32 v138, 16, v138
	v_add3_u32 v147, v183, v147, s80
	v_and_or_b32 v182, v147, s81, v138
	v_bfe_u32 v138, v168, 16, 1
	v_add3_u32 v138, v168, v138, s80
	v_bfe_u32 v147, v169, 16, 1
	v_lshrrev_b32_e32 v138, 16, v138
	v_add3_u32 v147, v169, v147, s80
	v_and_or_b32 v183, v147, s81, v138
	v_lshl_add_u64 v[168:169], v[150:151], 1, v[166:167]
	global_store_dwordx2 v[168:169], v[182:183], off
	s_and_b64 vcc, exec, s[6:7]
	s_mov_b64 s[68:69], -1
	s_cbranch_vccz .LBB0_1215
.LBB0_1242:
	s_and_b64 vcc, exec, s[68:69]
	s_cbranch_vccz .LBB0_1226
	v_pk_mul_f32 v[182:183], v[78:79], s[56:57] op_sel_hi:[1,0]
	v_pk_mul_f32 v[168:169], v[80:81], s[56:57] op_sel_hi:[1,0]
	v_bfe_u32 v138, v182, 16, 1
	v_add3_u32 v138, v182, v138, s80
	v_bfe_u32 v147, v183, 16, 1
	v_lshrrev_b32_e32 v138, 16, v138
	v_add3_u32 v147, v183, v147, s80
	v_and_or_b32 v182, v147, s81, v138
	v_bfe_u32 v138, v168, 16, 1
	v_add3_u32 v138, v168, v138, s80
	v_bfe_u32 v147, v169, 16, 1
	v_lshrrev_b32_e32 v138, 16, v138
	v_add3_u32 v147, v169, v147, s80
	v_and_or_b32 v183, v147, s81, v138
	v_lshl_add_u64 v[168:169], v[152:153], 1, v[166:167]
	global_store_dwordx2 v[168:169], v[182:183], off
	s_and_b64 vcc, exec, s[6:7]
	s_mov_b64 s[68:69], -1
	s_cbranch_vccz .LBB0_1227
.LBB0_1244:
	s_and_b64 vcc, exec, s[68:69]
	s_cbranch_vccz .LBB0_1246
	v_pk_mul_f32 v[160:161], v[74:75], s[56:57] op_sel_hi:[1,0]
	v_pk_mul_f32 v[158:159], v[76:77], s[56:57] op_sel_hi:[1,0]
	v_bfe_u32 v138, v160, 16, 1
	v_add3_u32 v138, v160, v138, s80
	v_bfe_u32 v147, v161, 16, 1
	v_lshrrev_b32_e32 v138, 16, v138
	v_add3_u32 v147, v161, v147, s80
	v_and_or_b32 v160, v147, s81, v138
	v_bfe_u32 v138, v158, 16, 1
	v_add3_u32 v138, v158, v138, s80
	v_bfe_u32 v147, v159, 16, 1
	v_lshrrev_b32_e32 v138, 16, v138
	v_add3_u32 v147, v159, v147, s80
	v_and_or_b32 v161, v147, s81, v138
	v_lshl_add_u64 v[158:159], v[156:157], 1, v[166:167]
	global_store_dwordx2 v[158:159], v[160:161], off
.LBB0_1246:
	v_add_u32_e32 v162, 48, v154
	v_ashrrev_i32_e32 v138, 10, v162
	v_and_b32_e32 v181, -2, v138
	v_lshrrev_b32_e32 v138, 3, v162
	v_and_b32_e32 v155, 0xfe, v138
	v_and_b32_e32 v138, 0x1fff, v162
	v_ashrrev_i32_e32 v163, 31, v162
	v_cmp_lt_u32_e64 s[8:9], s79, v138
	v_add_u32_e32 v138, 0xffffe200, v138
	v_lshlrev_b64 v[160:161], 9, v[162:163]
	v_lshlrev_b64 v[158:159], 10, v[162:163]
	v_ashrrev_i32_e32 v162, 13, v162
	v_lshlrev_b64 v[164:165], 10, v[138:139]
	s_and_b64 vcc, exec, s[6:7]
	s_mov_b64 s[68:69], -1
	s_cbranch_vccnz .LBB0_1294
	v_bfe_u32 v138, v94, 16, 1
	v_add3_u32 v138, v94, v138, s80
	v_bfe_u32 v147, v95, 16, 1
	v_lshrrev_b32_e32 v138, 16, v138
	v_add3_u32 v147, v95, v147, s80
	v_and_or_b32 v166, v147, s81, v138
	v_bfe_u32 v138, v96, 16, 1
	v_add3_u32 v138, v96, v138, s80
	v_bfe_u32 v147, v97, 16, 1
	v_lshrrev_b32_e32 v138, 16, v138
	v_add3_u32 v147, v97, v147, s80
	v_and_or_b32 v167, v147, s81, v138
	s_cmp_lt_i32 s10, 3
	s_cbranch_scc1 .LBB0_1255
	s_cmp_lg_u32 s10, 3
	s_cbranch_scc0 .LBB0_1252
	v_lshlrev_b32_e32 v182, 1, v146
	v_lshl_add_u64 v[168:169], s[50:51], 0, v[160:161]
	v_ashrrev_i32_e32 v183, 31, v182
	v_lshl_add_u64 v[168:169], v[168:169], 0, v[182:183]
	global_store_dwordx2 v[168:169], v[166:167], off
	s_and_saveexec_b64 s[68:69], s[8:9]
	s_cbranch_execz .LBB0_1251
	v_ashrrev_i32_e32 v163, 31, v162
	v_lshlrev_b64 v[168:169], 19, v[162:163]
	v_lshl_add_u64 v[168:169], s[52:53], 0, v[168:169]
	v_lshl_add_u64 v[168:169], v[168:169], 0, v[164:165]
	v_ashrrev_i32_e32 v147, 31, v146
	v_lshl_add_u64 v[168:169], v[146:147], 2, v[168:169]
	global_store_dwordx4 v[168:169], v[94:97], off

.LBB0_1252:
	s_andn2_b64 vcc, exec, s[68:69]
	s_cbranch_vccnz .LBB0_1254
	v_lshlrev_b32_e32 v182, 1, v146
	v_lshl_add_u64 v[168:169], s[24:25], 0, v[160:161]
	v_ashrrev_i32_e32 v183, 31, v182
	v_lshl_add_u64 v[168:169], v[168:169], 0, v[182:183]
	global_store_dwordx2 v[168:169], v[166:167], off
	v_lshl_add_u64 v[168:169], s[44:45], 0, v[158:159]
	v_ashrrev_i32_e32 v147, 31, v146
	v_lshl_add_u64 v[168:169], v[146:147], 2, v[168:169]
	global_store_dwordx4 v[168:169], v[94:97], off

.LBB0_1255:
	s_andn2_b64 vcc, exec, s[68:69]
	s_cbranch_vccnz .LBB0_1257
	v_ashrrev_i32_e32 v138, 7, v146
	v_add_u32_e32 v168, v181, v138
	v_ashrrev_i32_e32 v169, 31, v168
	v_lshrrev_b32_e32 v147, 6, v146
	v_lshlrev_b64 v[168:169], 8, v[168:169]
	v_and_or_b32 v138, v147, 1, v168
	v_or_b32_e32 v168, v138, v155
	v_lshlrev_b64 v[168:169], 10, v[168:169]
	v_and_or_b32 v138, v146, 60, v168
	v_or_b32_e32 v168, v138, v145
	v_lshl_add_u64 v[168:169], v[168:169], 1, s[46:47]
	global_store_dwordx2 v[168:169], v[166:167], off
	v_lshl_add_u64 v[166:167], s[48:49], 0, v[158:159]
	v_ashrrev_i32_e32 v147, 31, v146
	v_lshl_add_u64 v[166:167], v[146:147], 2, v[166:167]
	global_store_dwordx4 v[166:167], v[94:97], off

.LBB0_1259:
	v_bfe_u32 v138, v86, 16, 1
	v_add3_u32 v138, v86, v138, s80
	v_bfe_u32 v147, v87, 16, 1
	v_lshrrev_b32_e32 v138, 16, v138
	v_add3_u32 v147, v87, v147, s80
	v_and_or_b32 v168, v147, s81, v138
	v_bfe_u32 v138, v88, 16, 1
	v_add3_u32 v138, v88, v138, s80
	v_bfe_u32 v147, v89, 16, 1
	v_lshrrev_b32_e32 v138, 16, v138
	v_add3_u32 v147, v89, v147, s80
	v_and_or_b32 v169, v147, s81, v138
	s_cmp_lt_i32 s10, 3
	s_cbranch_scc1 .LBB0_1267
	s_cmp_lg_u32 s10, 3
	s_cbranch_scc0 .LBB0_1264
	v_lshlrev_b32_e32 v184, 1, v178
	v_lshl_add_u64 v[182:183], s[50:51], 0, v[160:161]
	v_ashrrev_i32_e32 v185, 31, v184
	v_lshl_add_u64 v[182:183], v[182:183], 0, v[184:185]
	global_store_dwordx2 v[182:183], v[168:169], off
	s_and_saveexec_b64 s[68:69], s[8:9]
	s_cbranch_execz .LBB0_1263
	v_ashrrev_i32_e32 v163, 31, v162
	v_lshlrev_b64 v[182:183], 19, v[162:163]
	v_lshl_add_u64 v[182:183], s[52:53], 0, v[182:183]
	v_lshl_add_u64 v[182:183], v[182:183], 0, v[164:165]
	v_ashrrev_i32_e32 v147, 31, v146
	v_lshl_add_u64 v[182:183], v[146:147], 2, v[182:183]
	global_store_dwordx4 v[182:183], v[86:89], off offset:64

.LBB0_1264:
	s_andn2_b64 vcc, exec, s[68:69]
	s_cbranch_vccnz .LBB0_1266
	v_lshlrev_b32_e32 v184, 1, v178
	v_lshl_add_u64 v[182:183], s[24:25], 0, v[160:161]
	v_ashrrev_i32_e32 v185, 31, v184
	v_lshl_add_u64 v[182:183], v[182:183], 0, v[184:185]
	global_store_dwordx2 v[182:183], v[168:169], off
	v_lshl_add_u64 v[182:183], s[44:45], 0, v[158:159]
	v_ashrrev_i32_e32 v147, 31, v146
	v_lshl_add_u64 v[182:183], v[146:147], 2, v[182:183]
	global_store_dwordx4 v[182:183], v[86:89], off offset:64

.LBB0_1267:
	s_andn2_b64 vcc, exec, s[68:69]
	s_cbranch_vccnz .LBB0_1269
	v_ashrrev_i32_e32 v138, 7, v178
	v_add_u32_e32 v182, v138, v181
	v_ashrrev_i32_e32 v183, 31, v182
	v_lshrrev_b32_e32 v147, 6, v178
	v_lshlrev_b64 v[182:183], 8, v[182:183]
	v_and_or_b32 v138, v147, 1, v182
	v_or_b32_e32 v182, v138, v155
	v_lshlrev_b64 v[182:183], 10, v[182:183]
	v_and_or_b32 v138, v178, 60, v182
	v_or_b32_e32 v182, v138, v145
	v_lshl_add_u64 v[182:183], v[182:183], 1, s[46:47]
	global_store_dwordx2 v[182:183], v[168:169], off
	v_lshl_add_u64 v[168:169], s[48:49], 0, v[158:159]
	v_ashrrev_i32_e32 v147, 31, v146
	v_lshl_add_u64 v[168:169], v[146:147], 2, v[168:169]
	global_store_dwordx4 v[168:169], v[86:89], off offset:64

.LBB0_1271:
	v_bfe_u32 v138, v70, 16, 1
	v_add3_u32 v138, v70, v138, s80
	v_bfe_u32 v147, v71, 16, 1
	v_lshrrev_b32_e32 v138, 16, v138
	v_add3_u32 v147, v71, v147, s80
	v_and_or_b32 v168, v147, s81, v138
	v_bfe_u32 v138, v72, 16, 1
	v_add3_u32 v138, v72, v138, s80
	v_bfe_u32 v147, v73, 16, 1
	v_lshrrev_b32_e32 v138, 16, v138
	v_add3_u32 v147, v73, v147, s80
	v_and_or_b32 v169, v147, s81, v138
	s_cmp_lt_i32 s10, 3
	s_cbranch_scc1 .LBB0_1279
	s_cmp_lg_u32 s10, 3
	s_cbranch_scc0 .LBB0_1276
	v_lshlrev_b32_e32 v184, 1, v180
	v_lshl_add_u64 v[182:183], s[50:51], 0, v[160:161]
	v_ashrrev_i32_e32 v185, 31, v184
	v_lshl_add_u64 v[182:183], v[182:183], 0, v[184:185]
	global_store_dwordx2 v[182:183], v[168:169], off
	s_and_saveexec_b64 s[68:69], s[8:9]
	s_cbranch_execz .LBB0_1275
	v_ashrrev_i32_e32 v163, 31, v162
	v_lshlrev_b64 v[182:183], 19, v[162:163]
	v_lshl_add_u64 v[182:183], s[52:53], 0, v[182:183]
	v_lshl_add_u64 v[182:183], v[182:183], 0, v[164:165]
	v_ashrrev_i32_e32 v147, 31, v146
	v_lshl_add_u64 v[182:183], v[146:147], 2, v[182:183]
	global_store_dwordx4 v[182:183], v[70:73], off offset:512

.LBB0_1276:
	s_andn2_b64 vcc, exec, s[68:69]
	s_cbranch_vccnz .LBB0_1278
	v_lshlrev_b32_e32 v184, 1, v180
	v_lshl_add_u64 v[182:183], s[24:25], 0, v[160:161]
	v_ashrrev_i32_e32 v185, 31, v184
	v_lshl_add_u64 v[182:183], v[182:183], 0, v[184:185]
	global_store_dwordx2 v[182:183], v[168:169], off
	v_lshl_add_u64 v[182:183], s[44:45], 0, v[158:159]
	v_ashrrev_i32_e32 v147, 31, v146
	v_lshl_add_u64 v[182:183], v[146:147], 2, v[182:183]
	global_store_dwordx4 v[182:183], v[70:73], off offset:512

.LBB0_1279:
	s_andn2_b64 vcc, exec, s[68:69]
	s_cbranch_vccnz .LBB0_1281
	v_ashrrev_i32_e32 v138, 7, v180
	v_add_u32_e32 v182, v138, v181
	v_ashrrev_i32_e32 v183, 31, v182
	v_lshrrev_b32_e32 v147, 6, v146
	v_lshlrev_b64 v[182:183], 8, v[182:183]
	v_and_or_b32 v138, v147, 1, v182
	v_or_b32_e32 v182, v138, v155
	v_lshlrev_b64 v[182:183], 10, v[182:183]
	v_and_or_b32 v138, v146, 60, v182
	v_or_b32_e32 v182, v138, v145
	v_lshl_add_u64 v[182:183], v[182:183], 1, s[46:47]
	global_store_dwordx2 v[182:183], v[168:169], off
	v_lshl_add_u64 v[168:169], s[48:49], 0, v[158:159]
	v_ashrrev_i32_e32 v147, 31, v146
	v_lshl_add_u64 v[168:169], v[146:147], 2, v[168:169]
	global_store_dwordx4 v[168:169], v[70:73], off offset:512

.LBB0_1283:
	v_bfe_u32 v138, v66, 16, 1
	v_add3_u32 v138, v66, v138, s80
	v_bfe_u32 v147, v67, 16, 1
	v_lshrrev_b32_e32 v138, 16, v138
	v_add3_u32 v147, v67, v147, s80
	v_and_or_b32 v168, v147, s81, v138
	v_bfe_u32 v138, v68, 16, 1
	v_add3_u32 v138, v68, v138, s80
	v_bfe_u32 v147, v69, 16, 1
	v_lshrrev_b32_e32 v138, 16, v138
	v_add3_u32 v147, v69, v147, s80
	v_and_or_b32 v169, v147, s81, v138
	s_cmp_lt_i32 s10, 3
	s_cbranch_scc1 .LBB0_1291
	s_cmp_lg_u32 s10, 3
	s_cbranch_scc0 .LBB0_1288
	v_lshlrev_b32_e32 v184, 1, v179
	v_lshl_add_u64 v[182:183], s[50:51], 0, v[160:161]
	v_ashrrev_i32_e32 v185, 31, v184
	v_lshl_add_u64 v[182:183], v[182:183], 0, v[184:185]
	global_store_dwordx2 v[182:183], v[168:169], off
	s_and_saveexec_b64 s[68:69], s[8:9]
	s_cbranch_execz .LBB0_1287
	v_ashrrev_i32_e32 v163, 31, v162
	v_lshlrev_b64 v[162:163], 19, v[162:163]
	v_lshl_add_u64 v[162:163], s[52:53], 0, v[162:163]
	v_lshl_add_u64 v[162:163], v[162:163], 0, v[164:165]
	v_ashrrev_i32_e32 v147, 31, v146
	v_lshl_add_u64 v[162:163], v[146:147], 2, v[162:163]
	global_store_dwordx4 v[162:163], v[66:69], off offset:576

.LBB0_1288:
	s_andn2_b64 vcc, exec, s[68:69]
	s_cbranch_vccnz .LBB0_1290
	v_lshlrev_b32_e32 v162, 1, v179
	v_lshl_add_u64 v[160:161], s[24:25], 0, v[160:161]
	v_ashrrev_i32_e32 v163, 31, v162
	v_lshl_add_u64 v[160:161], v[160:161], 0, v[162:163]
	global_store_dwordx2 v[160:161], v[168:169], off
	v_lshl_add_u64 v[160:161], s[44:45], 0, v[158:159]
	v_ashrrev_i32_e32 v147, 31, v146
	v_lshl_add_u64 v[160:161], v[146:147], 2, v[160:161]
	global_store_dwordx4 v[160:161], v[66:69], off offset:576

.LBB0_1291:
	s_andn2_b64 vcc, exec, s[68:69]
	s_cbranch_vccnz .LBB0_1293
	v_ashrrev_i32_e32 v138, 7, v179
	v_add_u32_e32 v160, v138, v181
	v_ashrrev_i32_e32 v161, 31, v160
	v_lshrrev_b32_e32 v147, 6, v179
	v_lshlrev_b64 v[160:161], 8, v[160:161]
	v_and_or_b32 v138, v147, 1, v160
	v_or_b32_e32 v160, v138, v155
	v_lshlrev_b64 v[160:161], 10, v[160:161]
	v_and_or_b32 v138, v179, 60, v160
	v_or_b32_e32 v160, v138, v145
	v_lshl_add_u64 v[158:159], s[48:49], 0, v[158:159]
	v_ashrrev_i32_e32 v147, 31, v146
	v_lshl_add_u64 v[160:161], v[160:161], 1, s[46:47]
	v_lshl_add_u64 v[158:159], v[146:147], 2, v[158:159]
	global_store_dwordx2 v[160:161], v[168:169], off
	global_store_dwordx4 v[158:159], v[66:69], off offset:576

.LBB0_1294:
	s_and_b64 vcc, exec, s[68:69]
	v_lshl_add_u64 v[166:167], s[54:55], 0, v[158:159]
	s_cbranch_vccz .LBB0_1258
	v_pk_mul_f32 v[182:183], v[94:95], s[56:57] op_sel_hi:[1,0]
	v_pk_mul_f32 v[168:169], v[96:97], s[56:57] op_sel_hi:[1,0]
	v_bfe_u32 v138, v182, 16, 1
	v_add3_u32 v138, v182, v138, s80
	v_bfe_u32 v147, v183, 16, 1
	v_lshrrev_b32_e32 v138, 16, v138
	v_add3_u32 v147, v183, v147, s80
	v_and_or_b32 v182, v147, s81, v138
	v_bfe_u32 v138, v168, 16, 1
	v_add3_u32 v138, v168, v138, s80
	v_bfe_u32 v147, v169, 16, 1
	v_lshrrev_b32_e32 v138, 16, v138
	v_add3_u32 v147, v169, v147, s80
	v_and_or_b32 v183, v147, s81, v138
	v_lshl_add_u64 v[168:169], v[148:149], 1, v[166:167]
	global_store_dwordx2 v[168:169], v[182:183], off
	s_and_b64 vcc, exec, s[6:7]
	s_mov_b64 s[68:69], -1
	s_cbranch_vccz .LBB0_1259
.LBB0_1296:
	s_and_b64 vcc, exec, s[68:69]
	s_cbranch_vccz .LBB0_1270
	v_pk_mul_f32 v[182:183], v[86:87], s[56:57] op_sel_hi:[1,0]
	v_pk_mul_f32 v[168:169], v[88:89], s[56:57] op_sel_hi:[1,0]
	v_bfe_u32 v138, v182, 16, 1
	v_add3_u32 v138, v182, v138, s80
	v_bfe_u32 v147, v183, 16, 1
	v_lshrrev_b32_e32 v138, 16, v138
	v_add3_u32 v147, v183, v147, s80
	v_and_or_b32 v182, v147, s81, v138
	v_bfe_u32 v138, v168, 16, 1
	v_add3_u32 v138, v168, v138, s80
	v_bfe_u32 v147, v169, 16, 1
	v_lshrrev_b32_e32 v138, 16, v138
	v_add3_u32 v147, v169, v147, s80
	v_and_or_b32 v183, v147, s81, v138
	v_lshl_add_u64 v[168:169], v[150:151], 1, v[166:167]
	global_store_dwordx2 v[168:169], v[182:183], off
	s_and_b64 vcc, exec, s[6:7]
	s_mov_b64 s[68:69], -1
	s_cbranch_vccz .LBB0_1271
.LBB0_1298:
	s_and_b64 vcc, exec, s[68:69]
	s_cbranch_vccz .LBB0_1282
	v_pk_mul_f32 v[182:183], v[70:71], s[56:57] op_sel_hi:[1,0]
	v_pk_mul_f32 v[168:169], v[72:73], s[56:57] op_sel_hi:[1,0]
	v_bfe_u32 v138, v182, 16, 1
	v_add3_u32 v138, v182, v138, s80
	v_bfe_u32 v147, v183, 16, 1
	v_lshrrev_b32_e32 v138, 16, v138
	v_add3_u32 v147, v183, v147, s80
	v_and_or_b32 v182, v147, s81, v138
	v_bfe_u32 v138, v168, 16, 1
	v_add3_u32 v138, v168, v138, s80
	v_bfe_u32 v147, v169, 16, 1
	v_lshrrev_b32_e32 v138, 16, v138
	v_add3_u32 v147, v169, v147, s80
	v_and_or_b32 v183, v147, s81, v138
	v_lshl_add_u64 v[168:169], v[152:153], 1, v[166:167]
	global_store_dwordx2 v[168:169], v[182:183], off
	s_and_b64 vcc, exec, s[6:7]
	s_mov_b64 s[68:69], -1
	s_cbranch_vccz .LBB0_1283
.LBB0_1300:
	s_and_b64 vcc, exec, s[68:69]
	s_cbranch_vccz .LBB0_1302
	v_pk_mul_f32 v[160:161], v[66:67], s[56:57] op_sel_hi:[1,0]
	v_pk_mul_f32 v[158:159], v[68:69], s[56:57] op_sel_hi:[1,0]
	v_bfe_u32 v138, v160, 16, 1
	v_add3_u32 v138, v160, v138, s80
	v_bfe_u32 v147, v161, 16, 1
	v_lshrrev_b32_e32 v138, 16, v138
	v_add3_u32 v147, v161, v147, s80
	v_and_or_b32 v160, v147, s81, v138
	v_bfe_u32 v138, v158, 16, 1
	v_add3_u32 v138, v158, v138, s80
	v_bfe_u32 v147, v159, 16, 1
	v_lshrrev_b32_e32 v138, 16, v138
	v_add3_u32 v147, v159, v147, s80
	v_and_or_b32 v161, v147, s81, v138
	v_lshl_add_u64 v[158:159], v[156:157], 1, v[166:167]
	global_store_dwordx2 v[158:159], v[160:161], off
.LBB0_1302:
	v_add_u32_e32 v162, 0x80, v154
	v_ashrrev_i32_e32 v138, 10, v162
	v_and_b32_e32 v181, -2, v138
	v_lshrrev_b32_e32 v138, 3, v162
	v_and_b32_e32 v155, 0xfe, v138
	v_and_b32_e32 v138, 0x1fff, v162
	v_ashrrev_i32_e32 v163, 31, v162
	v_cmp_lt_u32_e64 s[8:9], s79, v138
	v_add_u32_e32 v138, 0xffffe200, v138
	v_lshlrev_b64 v[160:161], 9, v[162:163]
	v_lshlrev_b64 v[158:159], 10, v[162:163]
	v_ashrrev_i32_e32 v162, 13, v162
	v_lshlrev_b64 v[164:165], 10, v[138:139]
	s_and_b64 vcc, exec, s[6:7]
	s_mov_b64 s[68:69], -1
	s_cbranch_vccnz .LBB0_1350
	v_bfe_u32 v138, v62, 16, 1
	v_add3_u32 v138, v62, v138, s80
	v_bfe_u32 v147, v63, 16, 1
	v_lshrrev_b32_e32 v138, 16, v138
	v_add3_u32 v147, v63, v147, s80
	v_and_or_b32 v166, v147, s81, v138
	v_bfe_u32 v138, v64, 16, 1
	v_add3_u32 v138, v64, v138, s80
	v_bfe_u32 v147, v65, 16, 1
	v_lshrrev_b32_e32 v138, 16, v138
	v_add3_u32 v147, v65, v147, s80
	v_and_or_b32 v167, v147, s81, v138
	s_cmp_lt_i32 s10, 3
	s_cbranch_scc1 .LBB0_1311
	s_cmp_lg_u32 s10, 3
	s_cbranch_scc0 .LBB0_1308
	v_lshlrev_b32_e32 v182, 1, v146
	v_lshl_add_u64 v[168:169], s[50:51], 0, v[160:161]
	v_ashrrev_i32_e32 v183, 31, v182
	v_lshl_add_u64 v[168:169], v[168:169], 0, v[182:183]
	global_store_dwordx2 v[168:169], v[166:167], off
	s_and_saveexec_b64 s[68:69], s[8:9]
	s_cbranch_execz .LBB0_1307
	v_ashrrev_i32_e32 v163, 31, v162
	v_lshlrev_b64 v[168:169], 19, v[162:163]
	v_lshl_add_u64 v[168:169], s[52:53], 0, v[168:169]
	v_lshl_add_u64 v[168:169], v[168:169], 0, v[164:165]
	v_ashrrev_i32_e32 v147, 31, v146
	v_lshl_add_u64 v[168:169], v[146:147], 2, v[168:169]
	global_store_dwordx4 v[168:169], v[62:65], off

.LBB0_1308:
	s_andn2_b64 vcc, exec, s[68:69]
	s_cbranch_vccnz .LBB0_1310
	v_lshlrev_b32_e32 v182, 1, v146
	v_lshl_add_u64 v[168:169], s[24:25], 0, v[160:161]
	v_ashrrev_i32_e32 v183, 31, v182
	v_lshl_add_u64 v[168:169], v[168:169], 0, v[182:183]
	global_store_dwordx2 v[168:169], v[166:167], off
	v_lshl_add_u64 v[168:169], s[44:45], 0, v[158:159]
	v_ashrrev_i32_e32 v147, 31, v146
	v_lshl_add_u64 v[168:169], v[146:147], 2, v[168:169]
	global_store_dwordx4 v[168:169], v[62:65], off

.LBB0_1311:
	s_andn2_b64 vcc, exec, s[68:69]
	s_cbranch_vccnz .LBB0_1313
	v_ashrrev_i32_e32 v138, 7, v146
	v_add_u32_e32 v168, v181, v138
	v_ashrrev_i32_e32 v169, 31, v168
	v_lshrrev_b32_e32 v147, 6, v146
	v_lshlrev_b64 v[168:169], 8, v[168:169]
	v_and_or_b32 v138, v147, 1, v168
	v_or_b32_e32 v168, v138, v155
	v_lshlrev_b64 v[168:169], 10, v[168:169]
	v_and_or_b32 v138, v146, 60, v168
	v_or_b32_e32 v168, v138, v145
	v_lshl_add_u64 v[168:169], v[168:169], 1, s[46:47]
	global_store_dwordx2 v[168:169], v[166:167], off
	v_lshl_add_u64 v[166:167], s[48:49], 0, v[158:159]
	v_ashrrev_i32_e32 v147, 31, v146
	v_lshl_add_u64 v[166:167], v[146:147], 2, v[166:167]
	global_store_dwordx4 v[166:167], v[62:65], off

.LBB0_1315:
	v_bfe_u32 v138, v58, 16, 1
	v_add3_u32 v138, v58, v138, s80
	v_bfe_u32 v147, v59, 16, 1
	v_lshrrev_b32_e32 v138, 16, v138
	v_add3_u32 v147, v59, v147, s80
	v_and_or_b32 v168, v147, s81, v138
	v_bfe_u32 v138, v60, 16, 1
	v_add3_u32 v138, v60, v138, s80
	v_bfe_u32 v147, v61, 16, 1
	v_lshrrev_b32_e32 v138, 16, v138
	v_add3_u32 v147, v61, v147, s80
	v_and_or_b32 v169, v147, s81, v138
	s_cmp_lt_i32 s10, 3
	s_cbranch_scc1 .LBB0_1323
	s_cmp_lg_u32 s10, 3
	s_cbranch_scc0 .LBB0_1320
	v_lshlrev_b32_e32 v184, 1, v178
	v_lshl_add_u64 v[182:183], s[50:51], 0, v[160:161]
	v_ashrrev_i32_e32 v185, 31, v184
	v_lshl_add_u64 v[182:183], v[182:183], 0, v[184:185]
	global_store_dwordx2 v[182:183], v[168:169], off
	s_and_saveexec_b64 s[68:69], s[8:9]
	s_cbranch_execz .LBB0_1319
	v_ashrrev_i32_e32 v163, 31, v162
	v_lshlrev_b64 v[182:183], 19, v[162:163]
	v_lshl_add_u64 v[182:183], s[52:53], 0, v[182:183]
	v_lshl_add_u64 v[182:183], v[182:183], 0, v[164:165]
	v_ashrrev_i32_e32 v147, 31, v146
	v_lshl_add_u64 v[182:183], v[146:147], 2, v[182:183]
	global_store_dwordx4 v[182:183], v[58:61], off offset:64

.LBB0_1320:
	s_andn2_b64 vcc, exec, s[68:69]
	s_cbranch_vccnz .LBB0_1322
	v_lshlrev_b32_e32 v184, 1, v178
	v_lshl_add_u64 v[182:183], s[24:25], 0, v[160:161]
	v_ashrrev_i32_e32 v185, 31, v184
	v_lshl_add_u64 v[182:183], v[182:183], 0, v[184:185]
	global_store_dwordx2 v[182:183], v[168:169], off
	v_lshl_add_u64 v[182:183], s[44:45], 0, v[158:159]
	v_ashrrev_i32_e32 v147, 31, v146
	v_lshl_add_u64 v[182:183], v[146:147], 2, v[182:183]
	global_store_dwordx4 v[182:183], v[58:61], off offset:64

.LBB0_1323:
	s_andn2_b64 vcc, exec, s[68:69]
	s_cbranch_vccnz .LBB0_1325
	v_ashrrev_i32_e32 v138, 7, v178
	v_add_u32_e32 v182, v138, v181
	v_ashrrev_i32_e32 v183, 31, v182
	v_lshrrev_b32_e32 v147, 6, v178
	v_lshlrev_b64 v[182:183], 8, v[182:183]
	v_and_or_b32 v138, v147, 1, v182
	v_or_b32_e32 v182, v138, v155
	v_lshlrev_b64 v[182:183], 10, v[182:183]
	v_and_or_b32 v138, v178, 60, v182
	v_or_b32_e32 v182, v138, v145
	v_lshl_add_u64 v[182:183], v[182:183], 1, s[46:47]
	global_store_dwordx2 v[182:183], v[168:169], off
	v_lshl_add_u64 v[168:169], s[48:49], 0, v[158:159]
	v_ashrrev_i32_e32 v147, 31, v146
	v_lshl_add_u64 v[168:169], v[146:147], 2, v[168:169]
	global_store_dwordx4 v[168:169], v[58:61], off offset:64

.LBB0_1327:
	v_bfe_u32 v138, v42, 16, 1
	v_add3_u32 v138, v42, v138, s80
	v_bfe_u32 v147, v43, 16, 1
	v_lshrrev_b32_e32 v138, 16, v138
	v_add3_u32 v147, v43, v147, s80
	v_and_or_b32 v168, v147, s81, v138
	v_bfe_u32 v138, v44, 16, 1
	v_add3_u32 v138, v44, v138, s80
	v_bfe_u32 v147, v45, 16, 1
	v_lshrrev_b32_e32 v138, 16, v138
	v_add3_u32 v147, v45, v147, s80
	v_and_or_b32 v169, v147, s81, v138
	s_cmp_lt_i32 s10, 3
	s_cbranch_scc1 .LBB0_1335
	s_cmp_lg_u32 s10, 3
	s_cbranch_scc0 .LBB0_1332
	v_lshlrev_b32_e32 v184, 1, v180
	v_lshl_add_u64 v[182:183], s[50:51], 0, v[160:161]
	v_ashrrev_i32_e32 v185, 31, v184
	v_lshl_add_u64 v[182:183], v[182:183], 0, v[184:185]
	global_store_dwordx2 v[182:183], v[168:169], off
	s_and_saveexec_b64 s[68:69], s[8:9]
	s_cbranch_execz .LBB0_1331
	v_ashrrev_i32_e32 v163, 31, v162
	v_lshlrev_b64 v[182:183], 19, v[162:163]
	v_lshl_add_u64 v[182:183], s[52:53], 0, v[182:183]
	v_lshl_add_u64 v[182:183], v[182:183], 0, v[164:165]
	v_ashrrev_i32_e32 v147, 31, v146
	v_lshl_add_u64 v[182:183], v[146:147], 2, v[182:183]
	global_store_dwordx4 v[182:183], v[42:45], off offset:512

.LBB0_1332:
	s_andn2_b64 vcc, exec, s[68:69]
	s_cbranch_vccnz .LBB0_1334
	v_lshlrev_b32_e32 v184, 1, v180
	v_lshl_add_u64 v[182:183], s[24:25], 0, v[160:161]
	v_ashrrev_i32_e32 v185, 31, v184
	v_lshl_add_u64 v[182:183], v[182:183], 0, v[184:185]
	global_store_dwordx2 v[182:183], v[168:169], off
	v_lshl_add_u64 v[182:183], s[44:45], 0, v[158:159]
	v_ashrrev_i32_e32 v147, 31, v146
	v_lshl_add_u64 v[182:183], v[146:147], 2, v[182:183]
	global_store_dwordx4 v[182:183], v[42:45], off offset:512

.LBB0_1335:
	s_andn2_b64 vcc, exec, s[68:69]
	s_cbranch_vccnz .LBB0_1337
	v_ashrrev_i32_e32 v138, 7, v180
	v_add_u32_e32 v182, v138, v181
	v_ashrrev_i32_e32 v183, 31, v182
	v_lshrrev_b32_e32 v147, 6, v146
	v_lshlrev_b64 v[182:183], 8, v[182:183]
	v_and_or_b32 v138, v147, 1, v182
	v_or_b32_e32 v182, v138, v155
	v_lshlrev_b64 v[182:183], 10, v[182:183]
	v_and_or_b32 v138, v146, 60, v182
	v_or_b32_e32 v182, v138, v145
	v_lshl_add_u64 v[182:183], v[182:183], 1, s[46:47]
	global_store_dwordx2 v[182:183], v[168:169], off
	v_lshl_add_u64 v[168:169], s[48:49], 0, v[158:159]
	v_ashrrev_i32_e32 v147, 31, v146
	v_lshl_add_u64 v[168:169], v[146:147], 2, v[168:169]
	global_store_dwordx4 v[168:169], v[42:45], off offset:512

.LBB0_1339:
	v_bfe_u32 v138, v34, 16, 1
	v_add3_u32 v138, v34, v138, s80
	v_bfe_u32 v147, v35, 16, 1
	v_lshrrev_b32_e32 v138, 16, v138
	v_add3_u32 v147, v35, v147, s80
	v_and_or_b32 v168, v147, s81, v138
	v_bfe_u32 v138, v36, 16, 1
	v_add3_u32 v138, v36, v138, s80
	v_bfe_u32 v147, v37, 16, 1
	v_lshrrev_b32_e32 v138, 16, v138
	v_add3_u32 v147, v37, v147, s80
	v_and_or_b32 v169, v147, s81, v138
	s_cmp_lt_i32 s10, 3
	s_cbranch_scc1 .LBB0_1347
	s_cmp_lg_u32 s10, 3
	s_cbranch_scc0 .LBB0_1344
	v_lshlrev_b32_e32 v184, 1, v179
	v_lshl_add_u64 v[182:183], s[50:51], 0, v[160:161]
	v_ashrrev_i32_e32 v185, 31, v184
	v_lshl_add_u64 v[182:183], v[182:183], 0, v[184:185]
	global_store_dwordx2 v[182:183], v[168:169], off
	s_and_saveexec_b64 s[68:69], s[8:9]
	s_cbranch_execz .LBB0_1343
	v_ashrrev_i32_e32 v163, 31, v162
	v_lshlrev_b64 v[162:163], 19, v[162:163]
	v_lshl_add_u64 v[162:163], s[52:53], 0, v[162:163]
	v_lshl_add_u64 v[162:163], v[162:163], 0, v[164:165]
	v_ashrrev_i32_e32 v147, 31, v146
	v_lshl_add_u64 v[162:163], v[146:147], 2, v[162:163]
	global_store_dwordx4 v[162:163], v[34:37], off offset:576

.LBB0_1344:
	s_andn2_b64 vcc, exec, s[68:69]
	s_cbranch_vccnz .LBB0_1346
	v_lshlrev_b32_e32 v162, 1, v179
	v_lshl_add_u64 v[160:161], s[24:25], 0, v[160:161]
	v_ashrrev_i32_e32 v163, 31, v162
	v_lshl_add_u64 v[160:161], v[160:161], 0, v[162:163]
	global_store_dwordx2 v[160:161], v[168:169], off
	v_lshl_add_u64 v[160:161], s[44:45], 0, v[158:159]
	v_ashrrev_i32_e32 v147, 31, v146
	v_lshl_add_u64 v[160:161], v[146:147], 2, v[160:161]
	global_store_dwordx4 v[160:161], v[34:37], off offset:576

.LBB0_1347:
	s_andn2_b64 vcc, exec, s[68:69]
	s_cbranch_vccnz .LBB0_1349
	v_ashrrev_i32_e32 v138, 7, v179
	v_add_u32_e32 v160, v138, v181
	v_ashrrev_i32_e32 v161, 31, v160
	v_lshrrev_b32_e32 v147, 6, v179
	v_lshlrev_b64 v[160:161], 8, v[160:161]
	v_and_or_b32 v138, v147, 1, v160
	v_or_b32_e32 v160, v138, v155
	v_lshlrev_b64 v[160:161], 10, v[160:161]
	v_and_or_b32 v138, v179, 60, v160
	v_or_b32_e32 v160, v138, v145
	v_lshl_add_u64 v[158:159], s[48:49], 0, v[158:159]
	v_ashrrev_i32_e32 v147, 31, v146
	v_lshl_add_u64 v[160:161], v[160:161], 1, s[46:47]
	v_lshl_add_u64 v[158:159], v[146:147], 2, v[158:159]
	global_store_dwordx2 v[160:161], v[168:169], off
	global_store_dwordx4 v[158:159], v[34:37], off offset:576

.LBB0_1350:
	s_and_b64 vcc, exec, s[68:69]
	v_lshl_add_u64 v[166:167], s[54:55], 0, v[158:159]
	s_cbranch_vccz .LBB0_1314
	v_pk_mul_f32 v[182:183], v[62:63], s[56:57] op_sel_hi:[1,0]
	v_pk_mul_f32 v[168:169], v[64:65], s[56:57] op_sel_hi:[1,0]
	v_bfe_u32 v138, v182, 16, 1
	v_add3_u32 v138, v182, v138, s80
	v_bfe_u32 v147, v183, 16, 1
	v_lshrrev_b32_e32 v138, 16, v138
	v_add3_u32 v147, v183, v147, s80
	v_and_or_b32 v182, v147, s81, v138
	v_bfe_u32 v138, v168, 16, 1
	v_add3_u32 v138, v168, v138, s80
	v_bfe_u32 v147, v169, 16, 1
	v_lshrrev_b32_e32 v138, 16, v138
	v_add3_u32 v147, v169, v147, s80
	v_and_or_b32 v183, v147, s81, v138
	v_lshl_add_u64 v[168:169], v[148:149], 1, v[166:167]
	global_store_dwordx2 v[168:169], v[182:183], off
	s_and_b64 vcc, exec, s[6:7]
	s_mov_b64 s[68:69], -1
	s_cbranch_vccz .LBB0_1315
.LBB0_1352:
	s_and_b64 vcc, exec, s[68:69]
	s_cbranch_vccz .LBB0_1326
	v_pk_mul_f32 v[182:183], v[58:59], s[56:57] op_sel_hi:[1,0]
	v_pk_mul_f32 v[168:169], v[60:61], s[56:57] op_sel_hi:[1,0]
	v_bfe_u32 v138, v182, 16, 1
	v_add3_u32 v138, v182, v138, s80
	v_bfe_u32 v147, v183, 16, 1
	v_lshrrev_b32_e32 v138, 16, v138
	v_add3_u32 v147, v183, v147, s80
	v_and_or_b32 v182, v147, s81, v138
	v_bfe_u32 v138, v168, 16, 1
	v_add3_u32 v138, v168, v138, s80
	v_bfe_u32 v147, v169, 16, 1
	v_lshrrev_b32_e32 v138, 16, v138
	v_add3_u32 v147, v169, v147, s80
	v_and_or_b32 v183, v147, s81, v138
	v_lshl_add_u64 v[168:169], v[150:151], 1, v[166:167]
	global_store_dwordx2 v[168:169], v[182:183], off
	s_and_b64 vcc, exec, s[6:7]
	s_mov_b64 s[68:69], -1
	s_cbranch_vccz .LBB0_1327
.LBB0_1354:
	s_and_b64 vcc, exec, s[68:69]
	s_cbranch_vccz .LBB0_1338
	v_pk_mul_f32 v[182:183], v[42:43], s[56:57] op_sel_hi:[1,0]
	v_pk_mul_f32 v[168:169], v[44:45], s[56:57] op_sel_hi:[1,0]
	v_bfe_u32 v138, v182, 16, 1
	v_add3_u32 v138, v182, v138, s80
	v_bfe_u32 v147, v183, 16, 1
	v_lshrrev_b32_e32 v138, 16, v138
	v_add3_u32 v147, v183, v147, s80
	v_and_or_b32 v182, v147, s81, v138
	v_bfe_u32 v138, v168, 16, 1
	v_add3_u32 v138, v168, v138, s80
	v_bfe_u32 v147, v169, 16, 1
	v_lshrrev_b32_e32 v138, 16, v138
	v_add3_u32 v147, v169, v147, s80
	v_and_or_b32 v183, v147, s81, v138
	v_lshl_add_u64 v[168:169], v[152:153], 1, v[166:167]
	global_store_dwordx2 v[168:169], v[182:183], off
	s_and_b64 vcc, exec, s[6:7]
	s_mov_b64 s[68:69], -1
	s_cbranch_vccz .LBB0_1339
.LBB0_1356:
	s_and_b64 vcc, exec, s[68:69]
	s_cbranch_vccz .LBB0_1358
	v_pk_mul_f32 v[160:161], v[34:35], s[56:57] op_sel_hi:[1,0]
	v_pk_mul_f32 v[158:159], v[36:37], s[56:57] op_sel_hi:[1,0]
	v_bfe_u32 v138, v160, 16, 1
	v_add3_u32 v138, v160, v138, s80
	v_bfe_u32 v147, v161, 16, 1
	v_lshrrev_b32_e32 v138, 16, v138
	v_add3_u32 v147, v161, v147, s80
	v_and_or_b32 v160, v147, s81, v138
	v_bfe_u32 v138, v158, 16, 1
	v_add3_u32 v138, v158, v138, s80
	v_bfe_u32 v147, v159, 16, 1
	v_lshrrev_b32_e32 v138, 16, v138
	v_add3_u32 v147, v159, v147, s80
	v_and_or_b32 v161, v147, s81, v138
	v_lshl_add_u64 v[158:159], v[156:157], 1, v[166:167]
	global_store_dwordx2 v[158:159], v[160:161], off
.LBB0_1358:
	v_add_u32_e32 v162, 0x90, v154
	v_ashrrev_i32_e32 v138, 10, v162
	v_and_b32_e32 v181, -2, v138
	v_lshrrev_b32_e32 v138, 3, v162
	v_and_b32_e32 v155, 0xfe, v138
	v_and_b32_e32 v138, 0x1fff, v162
	v_ashrrev_i32_e32 v163, 31, v162
	v_cmp_lt_u32_e64 s[8:9], s79, v138
	v_add_u32_e32 v138, 0xffffe200, v138
	v_lshlrev_b64 v[160:161], 9, v[162:163]
	v_lshlrev_b64 v[158:159], 10, v[162:163]
	v_ashrrev_i32_e32 v162, 13, v162
	v_lshlrev_b64 v[164:165], 10, v[138:139]
	s_and_b64 vcc, exec, s[6:7]
	s_mov_b64 s[68:69], -1
	s_cbranch_vccnz .LBB0_1406
	v_bfe_u32 v138, v54, 16, 1
	v_add3_u32 v138, v54, v138, s80
	v_bfe_u32 v147, v55, 16, 1
	v_lshrrev_b32_e32 v138, 16, v138
	v_add3_u32 v147, v55, v147, s80
	v_and_or_b32 v166, v147, s81, v138
	v_bfe_u32 v138, v56, 16, 1
	v_add3_u32 v138, v56, v138, s80
	v_bfe_u32 v147, v57, 16, 1
	v_lshrrev_b32_e32 v138, 16, v138
	v_add3_u32 v147, v57, v147, s80
	v_and_or_b32 v167, v147, s81, v138
	s_cmp_lt_i32 s10, 3
	s_cbranch_scc1 .LBB0_1367
	s_cmp_lg_u32 s10, 3
	s_cbranch_scc0 .LBB0_1364
	v_lshlrev_b32_e32 v182, 1, v146
	v_lshl_add_u64 v[168:169], s[50:51], 0, v[160:161]
	v_ashrrev_i32_e32 v183, 31, v182
	v_lshl_add_u64 v[168:169], v[168:169], 0, v[182:183]
	global_store_dwordx2 v[168:169], v[166:167], off
	s_and_saveexec_b64 s[68:69], s[8:9]
	s_cbranch_execz .LBB0_1363
	v_ashrrev_i32_e32 v163, 31, v162
	v_lshlrev_b64 v[168:169], 19, v[162:163]
	v_lshl_add_u64 v[168:169], s[52:53], 0, v[168:169]
	v_lshl_add_u64 v[168:169], v[168:169], 0, v[164:165]
	v_ashrrev_i32_e32 v147, 31, v146
	v_lshl_add_u64 v[168:169], v[146:147], 2, v[168:169]
	global_store_dwordx4 v[168:169], v[54:57], off

.LBB0_1364:
	s_andn2_b64 vcc, exec, s[68:69]
	s_cbranch_vccnz .LBB0_1366
	v_lshlrev_b32_e32 v182, 1, v146
	v_lshl_add_u64 v[168:169], s[24:25], 0, v[160:161]
	v_ashrrev_i32_e32 v183, 31, v182
	v_lshl_add_u64 v[168:169], v[168:169], 0, v[182:183]
	global_store_dwordx2 v[168:169], v[166:167], off
	v_lshl_add_u64 v[168:169], s[44:45], 0, v[158:159]
	v_ashrrev_i32_e32 v147, 31, v146
	v_lshl_add_u64 v[168:169], v[146:147], 2, v[168:169]
	global_store_dwordx4 v[168:169], v[54:57], off

.LBB0_1367:
	s_andn2_b64 vcc, exec, s[68:69]
	s_cbranch_vccnz .LBB0_1369
	v_ashrrev_i32_e32 v138, 7, v146
	v_add_u32_e32 v168, v181, v138
	v_ashrrev_i32_e32 v169, 31, v168
	v_lshrrev_b32_e32 v147, 6, v146
	v_lshlrev_b64 v[168:169], 8, v[168:169]
	v_and_or_b32 v138, v147, 1, v168
	v_or_b32_e32 v168, v138, v155
	v_lshlrev_b64 v[168:169], 10, v[168:169]
	v_and_or_b32 v138, v146, 60, v168
	v_or_b32_e32 v168, v138, v145
	v_lshl_add_u64 v[168:169], v[168:169], 1, s[46:47]
	global_store_dwordx2 v[168:169], v[166:167], off
	v_lshl_add_u64 v[166:167], s[48:49], 0, v[158:159]
	v_ashrrev_i32_e32 v147, 31, v146
	v_lshl_add_u64 v[166:167], v[146:147], 2, v[166:167]
	global_store_dwordx4 v[166:167], v[54:57], off

.LBB0_1371:
	v_bfe_u32 v138, v50, 16, 1
	v_add3_u32 v138, v50, v138, s80
	v_bfe_u32 v147, v51, 16, 1
	v_lshrrev_b32_e32 v138, 16, v138
	v_add3_u32 v147, v51, v147, s80
	v_and_or_b32 v168, v147, s81, v138
	v_bfe_u32 v138, v52, 16, 1
	v_add3_u32 v138, v52, v138, s80
	v_bfe_u32 v147, v53, 16, 1
	v_lshrrev_b32_e32 v138, 16, v138
	v_add3_u32 v147, v53, v147, s80
	v_and_or_b32 v169, v147, s81, v138
	s_cmp_lt_i32 s10, 3
	s_cbranch_scc1 .LBB0_1379
	s_cmp_lg_u32 s10, 3
	s_cbranch_scc0 .LBB0_1376
	v_lshlrev_b32_e32 v184, 1, v178
	v_lshl_add_u64 v[182:183], s[50:51], 0, v[160:161]
	v_ashrrev_i32_e32 v185, 31, v184
	v_lshl_add_u64 v[182:183], v[182:183], 0, v[184:185]
	global_store_dwordx2 v[182:183], v[168:169], off
	s_and_saveexec_b64 s[68:69], s[8:9]
	s_cbranch_execz .LBB0_1375
	v_ashrrev_i32_e32 v163, 31, v162
	v_lshlrev_b64 v[182:183], 19, v[162:163]
	v_lshl_add_u64 v[182:183], s[52:53], 0, v[182:183]
	v_lshl_add_u64 v[182:183], v[182:183], 0, v[164:165]
	v_ashrrev_i32_e32 v147, 31, v146
	v_lshl_add_u64 v[182:183], v[146:147], 2, v[182:183]
	global_store_dwordx4 v[182:183], v[50:53], off offset:64

.LBB0_1376:
	s_andn2_b64 vcc, exec, s[68:69]
	s_cbranch_vccnz .LBB0_1378
	v_lshlrev_b32_e32 v184, 1, v178
	v_lshl_add_u64 v[182:183], s[24:25], 0, v[160:161]
	v_ashrrev_i32_e32 v185, 31, v184
	v_lshl_add_u64 v[182:183], v[182:183], 0, v[184:185]
	global_store_dwordx2 v[182:183], v[168:169], off
	v_lshl_add_u64 v[182:183], s[44:45], 0, v[158:159]
	v_ashrrev_i32_e32 v147, 31, v146
	v_lshl_add_u64 v[182:183], v[146:147], 2, v[182:183]
	global_store_dwordx4 v[182:183], v[50:53], off offset:64

.LBB0_1379:
	s_andn2_b64 vcc, exec, s[68:69]
	s_cbranch_vccnz .LBB0_1381
	v_ashrrev_i32_e32 v138, 7, v178
	v_add_u32_e32 v182, v138, v181
	v_ashrrev_i32_e32 v183, 31, v182
	v_lshrrev_b32_e32 v147, 6, v178
	v_lshlrev_b64 v[182:183], 8, v[182:183]
	v_and_or_b32 v138, v147, 1, v182
	v_or_b32_e32 v182, v138, v155
	v_lshlrev_b64 v[182:183], 10, v[182:183]
	v_and_or_b32 v138, v178, 60, v182
	v_or_b32_e32 v182, v138, v145
	v_lshl_add_u64 v[182:183], v[182:183], 1, s[46:47]
	global_store_dwordx2 v[182:183], v[168:169], off
	v_lshl_add_u64 v[168:169], s[48:49], 0, v[158:159]
	v_ashrrev_i32_e32 v147, 31, v146
	v_lshl_add_u64 v[168:169], v[146:147], 2, v[168:169]
	global_store_dwordx4 v[168:169], v[50:53], off offset:64

.LBB0_1383:
	v_bfe_u32 v138, v26, 16, 1
	v_add3_u32 v138, v26, v138, s80
	v_bfe_u32 v147, v27, 16, 1
	v_lshrrev_b32_e32 v138, 16, v138
	v_add3_u32 v147, v27, v147, s80
	v_and_or_b32 v168, v147, s81, v138
	v_bfe_u32 v138, v28, 16, 1
	v_add3_u32 v138, v28, v138, s80
	v_bfe_u32 v147, v29, 16, 1
	v_lshrrev_b32_e32 v138, 16, v138
	v_add3_u32 v147, v29, v147, s80
	v_and_or_b32 v169, v147, s81, v138
	s_cmp_lt_i32 s10, 3
	s_cbranch_scc1 .LBB0_1391
	s_cmp_lg_u32 s10, 3
	s_cbranch_scc0 .LBB0_1388
	v_lshlrev_b32_e32 v184, 1, v180
	v_lshl_add_u64 v[182:183], s[50:51], 0, v[160:161]
	v_ashrrev_i32_e32 v185, 31, v184
	v_lshl_add_u64 v[182:183], v[182:183], 0, v[184:185]
	global_store_dwordx2 v[182:183], v[168:169], off
	s_and_saveexec_b64 s[68:69], s[8:9]
	s_cbranch_execz .LBB0_1387
	v_ashrrev_i32_e32 v163, 31, v162
	v_lshlrev_b64 v[182:183], 19, v[162:163]
	v_lshl_add_u64 v[182:183], s[52:53], 0, v[182:183]
	v_lshl_add_u64 v[182:183], v[182:183], 0, v[164:165]
	v_ashrrev_i32_e32 v147, 31, v146
	v_lshl_add_u64 v[182:183], v[146:147], 2, v[182:183]
	global_store_dwordx4 v[182:183], v[26:29], off offset:512

.LBB0_1388:
	s_andn2_b64 vcc, exec, s[68:69]
	s_cbranch_vccnz .LBB0_1390
	v_lshlrev_b32_e32 v184, 1, v180
	v_lshl_add_u64 v[182:183], s[24:25], 0, v[160:161]
	v_ashrrev_i32_e32 v185, 31, v184
	v_lshl_add_u64 v[182:183], v[182:183], 0, v[184:185]
	global_store_dwordx2 v[182:183], v[168:169], off
	v_lshl_add_u64 v[182:183], s[44:45], 0, v[158:159]
	v_ashrrev_i32_e32 v147, 31, v146
	v_lshl_add_u64 v[182:183], v[146:147], 2, v[182:183]
	global_store_dwordx4 v[182:183], v[26:29], off offset:512

.LBB0_1391:
	s_andn2_b64 vcc, exec, s[68:69]
	s_cbranch_vccnz .LBB0_1393
	v_ashrrev_i32_e32 v138, 7, v180
	v_add_u32_e32 v182, v138, v181
	v_ashrrev_i32_e32 v183, 31, v182
	v_lshrrev_b32_e32 v147, 6, v146
	v_lshlrev_b64 v[182:183], 8, v[182:183]
	v_and_or_b32 v138, v147, 1, v182
	v_or_b32_e32 v182, v138, v155
	v_lshlrev_b64 v[182:183], 10, v[182:183]
	v_and_or_b32 v138, v146, 60, v182
	v_or_b32_e32 v182, v138, v145
	v_lshl_add_u64 v[182:183], v[182:183], 1, s[46:47]
	global_store_dwordx2 v[182:183], v[168:169], off
	v_lshl_add_u64 v[168:169], s[48:49], 0, v[158:159]
	v_ashrrev_i32_e32 v147, 31, v146
	v_lshl_add_u64 v[168:169], v[146:147], 2, v[168:169]
	global_store_dwordx4 v[168:169], v[26:29], off offset:512

.LBB0_1395:
	v_bfe_u32 v138, v18, 16, 1
	v_add3_u32 v138, v18, v138, s80
	v_bfe_u32 v147, v19, 16, 1
	v_lshrrev_b32_e32 v138, 16, v138
	v_add3_u32 v147, v19, v147, s80
	v_and_or_b32 v168, v147, s81, v138
	v_bfe_u32 v138, v20, 16, 1
	v_add3_u32 v138, v20, v138, s80
	v_bfe_u32 v147, v21, 16, 1
	v_lshrrev_b32_e32 v138, 16, v138
	v_add3_u32 v147, v21, v147, s80
	v_and_or_b32 v169, v147, s81, v138
	s_cmp_lt_i32 s10, 3
	s_cbranch_scc1 .LBB0_1403
	s_cmp_lg_u32 s10, 3
	s_cbranch_scc0 .LBB0_1400
	v_lshlrev_b32_e32 v184, 1, v179
	v_lshl_add_u64 v[182:183], s[50:51], 0, v[160:161]
	v_ashrrev_i32_e32 v185, 31, v184
	v_lshl_add_u64 v[182:183], v[182:183], 0, v[184:185]
	global_store_dwordx2 v[182:183], v[168:169], off
	s_and_saveexec_b64 s[68:69], s[8:9]
	s_cbranch_execz .LBB0_1399
	v_ashrrev_i32_e32 v163, 31, v162
	v_lshlrev_b64 v[162:163], 19, v[162:163]
	v_lshl_add_u64 v[162:163], s[52:53], 0, v[162:163]
	v_lshl_add_u64 v[162:163], v[162:163], 0, v[164:165]
	v_ashrrev_i32_e32 v147, 31, v146
	v_lshl_add_u64 v[162:163], v[146:147], 2, v[162:163]
	global_store_dwordx4 v[162:163], v[18:21], off offset:576

.LBB0_1400:
	s_andn2_b64 vcc, exec, s[68:69]
	s_cbranch_vccnz .LBB0_1402
	v_lshlrev_b32_e32 v162, 1, v179
	v_lshl_add_u64 v[160:161], s[24:25], 0, v[160:161]
	v_ashrrev_i32_e32 v163, 31, v162
	v_lshl_add_u64 v[160:161], v[160:161], 0, v[162:163]
	global_store_dwordx2 v[160:161], v[168:169], off
	v_lshl_add_u64 v[160:161], s[44:45], 0, v[158:159]
	v_ashrrev_i32_e32 v147, 31, v146
	v_lshl_add_u64 v[160:161], v[146:147], 2, v[160:161]
	global_store_dwordx4 v[160:161], v[18:21], off offset:576

.LBB0_1403:
	s_andn2_b64 vcc, exec, s[68:69]
	s_cbranch_vccnz .LBB0_1405
	v_ashrrev_i32_e32 v138, 7, v179
	v_add_u32_e32 v160, v138, v181
	v_ashrrev_i32_e32 v161, 31, v160
	v_lshrrev_b32_e32 v147, 6, v179
	v_lshlrev_b64 v[160:161], 8, v[160:161]
	v_and_or_b32 v138, v147, 1, v160
	v_or_b32_e32 v160, v138, v155
	v_lshlrev_b64 v[160:161], 10, v[160:161]
	v_and_or_b32 v138, v179, 60, v160
	v_or_b32_e32 v160, v138, v145
	v_lshl_add_u64 v[158:159], s[48:49], 0, v[158:159]
	v_ashrrev_i32_e32 v147, 31, v146
	v_lshl_add_u64 v[160:161], v[160:161], 1, s[46:47]
	v_lshl_add_u64 v[158:159], v[146:147], 2, v[158:159]
	global_store_dwordx2 v[160:161], v[168:169], off
	global_store_dwordx4 v[158:159], v[18:21], off offset:576

.LBB0_1406:
	s_and_b64 vcc, exec, s[68:69]
	v_lshl_add_u64 v[166:167], s[54:55], 0, v[158:159]
	s_cbranch_vccz .LBB0_1370
	v_pk_mul_f32 v[182:183], v[54:55], s[56:57] op_sel_hi:[1,0]
	v_pk_mul_f32 v[168:169], v[56:57], s[56:57] op_sel_hi:[1,0]
	v_bfe_u32 v138, v182, 16, 1
	v_add3_u32 v138, v182, v138, s80
	v_bfe_u32 v147, v183, 16, 1
	v_lshrrev_b32_e32 v138, 16, v138
	v_add3_u32 v147, v183, v147, s80
	v_and_or_b32 v182, v147, s81, v138
	v_bfe_u32 v138, v168, 16, 1
	v_add3_u32 v138, v168, v138, s80
	v_bfe_u32 v147, v169, 16, 1
	v_lshrrev_b32_e32 v138, 16, v138
	v_add3_u32 v147, v169, v147, s80
	v_and_or_b32 v183, v147, s81, v138
	v_lshl_add_u64 v[168:169], v[148:149], 1, v[166:167]
	global_store_dwordx2 v[168:169], v[182:183], off
	s_and_b64 vcc, exec, s[6:7]
	s_mov_b64 s[68:69], -1
	s_cbranch_vccz .LBB0_1371
.LBB0_1408:
	s_and_b64 vcc, exec, s[68:69]
	s_cbranch_vccz .LBB0_1382
	v_pk_mul_f32 v[182:183], v[50:51], s[56:57] op_sel_hi:[1,0]
	v_pk_mul_f32 v[168:169], v[52:53], s[56:57] op_sel_hi:[1,0]
	v_bfe_u32 v138, v182, 16, 1
	v_add3_u32 v138, v182, v138, s80
	v_bfe_u32 v147, v183, 16, 1
	v_lshrrev_b32_e32 v138, 16, v138
	v_add3_u32 v147, v183, v147, s80
	v_and_or_b32 v182, v147, s81, v138
	v_bfe_u32 v138, v168, 16, 1
	v_add3_u32 v138, v168, v138, s80
	v_bfe_u32 v147, v169, 16, 1
	v_lshrrev_b32_e32 v138, 16, v138
	v_add3_u32 v147, v169, v147, s80
	v_and_or_b32 v183, v147, s81, v138
	v_lshl_add_u64 v[168:169], v[150:151], 1, v[166:167]
	global_store_dwordx2 v[168:169], v[182:183], off
	s_and_b64 vcc, exec, s[6:7]
	s_mov_b64 s[68:69], -1
	s_cbranch_vccz .LBB0_1383
.LBB0_1410:
	s_and_b64 vcc, exec, s[68:69]
	s_cbranch_vccz .LBB0_1394
	v_pk_mul_f32 v[182:183], v[26:27], s[56:57] op_sel_hi:[1,0]
	v_pk_mul_f32 v[168:169], v[28:29], s[56:57] op_sel_hi:[1,0]
	v_bfe_u32 v138, v182, 16, 1
	v_add3_u32 v138, v182, v138, s80
	v_bfe_u32 v147, v183, 16, 1
	v_lshrrev_b32_e32 v138, 16, v138
	v_add3_u32 v147, v183, v147, s80
	v_and_or_b32 v182, v147, s81, v138
	v_bfe_u32 v138, v168, 16, 1
	v_add3_u32 v138, v168, v138, s80
	v_bfe_u32 v147, v169, 16, 1
	v_lshrrev_b32_e32 v138, 16, v138
	v_add3_u32 v147, v169, v147, s80
	v_and_or_b32 v183, v147, s81, v138
	v_lshl_add_u64 v[168:169], v[152:153], 1, v[166:167]
	global_store_dwordx2 v[168:169], v[182:183], off
	s_and_b64 vcc, exec, s[6:7]
	s_mov_b64 s[68:69], -1
	s_cbranch_vccz .LBB0_1395
.LBB0_1412:
	s_and_b64 vcc, exec, s[68:69]
	s_cbranch_vccz .LBB0_1414
	v_pk_mul_f32 v[160:161], v[18:19], s[56:57] op_sel_hi:[1,0]
	v_pk_mul_f32 v[158:159], v[20:21], s[56:57] op_sel_hi:[1,0]
	v_bfe_u32 v138, v160, 16, 1
	v_add3_u32 v138, v160, v138, s80
	v_bfe_u32 v147, v161, 16, 1
	v_lshrrev_b32_e32 v138, 16, v138
	v_add3_u32 v147, v161, v147, s80
	v_and_or_b32 v160, v147, s81, v138
	v_bfe_u32 v138, v158, 16, 1
	v_add3_u32 v138, v158, v138, s80
	v_bfe_u32 v147, v159, 16, 1
	v_lshrrev_b32_e32 v138, 16, v138
	v_add3_u32 v147, v159, v147, s80
	v_and_or_b32 v161, v147, s81, v138
	v_lshl_add_u64 v[158:159], v[156:157], 1, v[166:167]
	global_store_dwordx2 v[158:159], v[160:161], off
.LBB0_1414:
	v_add_u32_e32 v162, 0xa0, v154
	v_ashrrev_i32_e32 v138, 10, v162
	v_and_b32_e32 v181, -2, v138
	v_lshrrev_b32_e32 v138, 3, v162
	v_and_b32_e32 v155, 0xfe, v138
	v_and_b32_e32 v138, 0x1fff, v162
	v_ashrrev_i32_e32 v163, 31, v162
	v_cmp_lt_u32_e64 s[8:9], s79, v138
	v_add_u32_e32 v138, 0xffffe200, v138
	v_lshlrev_b64 v[160:161], 9, v[162:163]
	v_lshlrev_b64 v[158:159], 10, v[162:163]
	v_ashrrev_i32_e32 v162, 13, v162
	v_lshlrev_b64 v[164:165], 10, v[138:139]
	s_and_b64 vcc, exec, s[6:7]
	s_mov_b64 s[68:69], -1
	s_cbranch_vccnz .LBB0_1462
	v_bfe_u32 v138, v46, 16, 1
	v_add3_u32 v138, v46, v138, s80
	v_bfe_u32 v147, v47, 16, 1
	v_lshrrev_b32_e32 v138, 16, v138
	v_add3_u32 v147, v47, v147, s80
	v_and_or_b32 v166, v147, s81, v138
	v_bfe_u32 v138, v48, 16, 1
	v_add3_u32 v138, v48, v138, s80
	v_bfe_u32 v147, v49, 16, 1
	v_lshrrev_b32_e32 v138, 16, v138
	v_add3_u32 v147, v49, v147, s80
	v_and_or_b32 v167, v147, s81, v138
	s_cmp_lt_i32 s10, 3
	s_cbranch_scc1 .LBB0_1423
	s_cmp_lg_u32 s10, 3
	s_cbranch_scc0 .LBB0_1420
	v_lshlrev_b32_e32 v182, 1, v146
	v_lshl_add_u64 v[168:169], s[50:51], 0, v[160:161]
	v_ashrrev_i32_e32 v183, 31, v182
	v_lshl_add_u64 v[168:169], v[168:169], 0, v[182:183]
	global_store_dwordx2 v[168:169], v[166:167], off
	s_and_saveexec_b64 s[68:69], s[8:9]
	s_cbranch_execz .LBB0_1419
	v_ashrrev_i32_e32 v163, 31, v162
	v_lshlrev_b64 v[168:169], 19, v[162:163]
	v_lshl_add_u64 v[168:169], s[52:53], 0, v[168:169]
	v_lshl_add_u64 v[168:169], v[168:169], 0, v[164:165]
	v_ashrrev_i32_e32 v147, 31, v146
	v_lshl_add_u64 v[168:169], v[146:147], 2, v[168:169]
	global_store_dwordx4 v[168:169], v[46:49], off

.LBB0_1420:
	s_andn2_b64 vcc, exec, s[68:69]
	s_cbranch_vccnz .LBB0_1422
	v_lshlrev_b32_e32 v182, 1, v146
	v_lshl_add_u64 v[168:169], s[24:25], 0, v[160:161]
	v_ashrrev_i32_e32 v183, 31, v182
	v_lshl_add_u64 v[168:169], v[168:169], 0, v[182:183]
	global_store_dwordx2 v[168:169], v[166:167], off
	v_lshl_add_u64 v[168:169], s[44:45], 0, v[158:159]
	v_ashrrev_i32_e32 v147, 31, v146
	v_lshl_add_u64 v[168:169], v[146:147], 2, v[168:169]
	global_store_dwordx4 v[168:169], v[46:49], off

.LBB0_1423:
	s_andn2_b64 vcc, exec, s[68:69]
	s_cbranch_vccnz .LBB0_1425
	v_ashrrev_i32_e32 v138, 7, v146
	v_add_u32_e32 v168, v181, v138
	v_ashrrev_i32_e32 v169, 31, v168
	v_lshrrev_b32_e32 v147, 6, v146
	v_lshlrev_b64 v[168:169], 8, v[168:169]
	v_and_or_b32 v138, v147, 1, v168
	v_or_b32_e32 v168, v138, v155
	v_lshlrev_b64 v[168:169], 10, v[168:169]
	v_and_or_b32 v138, v146, 60, v168
	v_or_b32_e32 v168, v138, v145
	v_lshl_add_u64 v[168:169], v[168:169], 1, s[46:47]
	global_store_dwordx2 v[168:169], v[166:167], off
	v_lshl_add_u64 v[166:167], s[48:49], 0, v[158:159]
	v_ashrrev_i32_e32 v147, 31, v146
	v_lshl_add_u64 v[166:167], v[146:147], 2, v[166:167]
	global_store_dwordx4 v[166:167], v[46:49], off

.LBB0_1427:
	v_bfe_u32 v138, v38, 16, 1
	v_add3_u32 v138, v38, v138, s80
	v_bfe_u32 v147, v39, 16, 1
	v_lshrrev_b32_e32 v138, 16, v138
	v_add3_u32 v147, v39, v147, s80
	v_and_or_b32 v168, v147, s81, v138
	v_bfe_u32 v138, v40, 16, 1
	v_add3_u32 v138, v40, v138, s80
	v_bfe_u32 v147, v41, 16, 1
	v_lshrrev_b32_e32 v138, 16, v138
	v_add3_u32 v147, v41, v147, s80
	v_and_or_b32 v169, v147, s81, v138
	s_cmp_lt_i32 s10, 3
	s_cbranch_scc1 .LBB0_1435
	s_cmp_lg_u32 s10, 3
	s_cbranch_scc0 .LBB0_1432
	v_lshlrev_b32_e32 v184, 1, v178
	v_lshl_add_u64 v[182:183], s[50:51], 0, v[160:161]
	v_ashrrev_i32_e32 v185, 31, v184
	v_lshl_add_u64 v[182:183], v[182:183], 0, v[184:185]
	global_store_dwordx2 v[182:183], v[168:169], off
	s_and_saveexec_b64 s[68:69], s[8:9]
	s_cbranch_execz .LBB0_1431
	v_ashrrev_i32_e32 v163, 31, v162
	v_lshlrev_b64 v[182:183], 19, v[162:163]
	v_lshl_add_u64 v[182:183], s[52:53], 0, v[182:183]
	v_lshl_add_u64 v[182:183], v[182:183], 0, v[164:165]
	v_ashrrev_i32_e32 v147, 31, v146
	v_lshl_add_u64 v[182:183], v[146:147], 2, v[182:183]
	global_store_dwordx4 v[182:183], v[38:41], off offset:64

.LBB0_1432:
	s_andn2_b64 vcc, exec, s[68:69]
	s_cbranch_vccnz .LBB0_1434
	v_lshlrev_b32_e32 v184, 1, v178
	v_lshl_add_u64 v[182:183], s[24:25], 0, v[160:161]
	v_ashrrev_i32_e32 v185, 31, v184
	v_lshl_add_u64 v[182:183], v[182:183], 0, v[184:185]
	global_store_dwordx2 v[182:183], v[168:169], off
	v_lshl_add_u64 v[182:183], s[44:45], 0, v[158:159]
	v_ashrrev_i32_e32 v147, 31, v146
	v_lshl_add_u64 v[182:183], v[146:147], 2, v[182:183]
	global_store_dwordx4 v[182:183], v[38:41], off offset:64

.LBB0_1435:
	s_andn2_b64 vcc, exec, s[68:69]
	s_cbranch_vccnz .LBB0_1437
	v_ashrrev_i32_e32 v138, 7, v178
	v_add_u32_e32 v182, v138, v181
	v_ashrrev_i32_e32 v183, 31, v182
	v_lshrrev_b32_e32 v147, 6, v178
	v_lshlrev_b64 v[182:183], 8, v[182:183]
	v_and_or_b32 v138, v147, 1, v182
	v_or_b32_e32 v182, v138, v155
	v_lshlrev_b64 v[182:183], 10, v[182:183]
	v_and_or_b32 v138, v178, 60, v182
	v_or_b32_e32 v182, v138, v145
	v_lshl_add_u64 v[182:183], v[182:183], 1, s[46:47]
	global_store_dwordx2 v[182:183], v[168:169], off
	v_lshl_add_u64 v[168:169], s[48:49], 0, v[158:159]
	v_ashrrev_i32_e32 v147, 31, v146
	v_lshl_add_u64 v[168:169], v[146:147], 2, v[168:169]
	global_store_dwordx4 v[168:169], v[38:41], off offset:64

.LBB0_1439:
	v_bfe_u32 v138, v14, 16, 1
	v_add3_u32 v138, v14, v138, s80
	v_bfe_u32 v147, v15, 16, 1
	v_lshrrev_b32_e32 v138, 16, v138
	v_add3_u32 v147, v15, v147, s80
	v_and_or_b32 v168, v147, s81, v138
	v_bfe_u32 v138, v16, 16, 1
	v_add3_u32 v138, v16, v138, s80
	v_bfe_u32 v147, v17, 16, 1
	v_lshrrev_b32_e32 v138, 16, v138
	v_add3_u32 v147, v17, v147, s80
	v_and_or_b32 v169, v147, s81, v138
	s_cmp_lt_i32 s10, 3
	s_cbranch_scc1 .LBB0_1447
	s_cmp_lg_u32 s10, 3
	s_cbranch_scc0 .LBB0_1444
	v_lshlrev_b32_e32 v184, 1, v180
	v_lshl_add_u64 v[182:183], s[50:51], 0, v[160:161]
	v_ashrrev_i32_e32 v185, 31, v184
	v_lshl_add_u64 v[182:183], v[182:183], 0, v[184:185]
	global_store_dwordx2 v[182:183], v[168:169], off
	s_and_saveexec_b64 s[68:69], s[8:9]
	s_cbranch_execz .LBB0_1443
	v_ashrrev_i32_e32 v163, 31, v162
	v_lshlrev_b64 v[182:183], 19, v[162:163]
	v_lshl_add_u64 v[182:183], s[52:53], 0, v[182:183]
	v_lshl_add_u64 v[182:183], v[182:183], 0, v[164:165]
	v_ashrrev_i32_e32 v147, 31, v146
	v_lshl_add_u64 v[182:183], v[146:147], 2, v[182:183]
	global_store_dwordx4 v[182:183], v[14:17], off offset:512

.LBB0_1444:
	s_andn2_b64 vcc, exec, s[68:69]
	s_cbranch_vccnz .LBB0_1446
	v_lshlrev_b32_e32 v184, 1, v180
	v_lshl_add_u64 v[182:183], s[24:25], 0, v[160:161]
	v_ashrrev_i32_e32 v185, 31, v184
	v_lshl_add_u64 v[182:183], v[182:183], 0, v[184:185]
	global_store_dwordx2 v[182:183], v[168:169], off
	v_lshl_add_u64 v[182:183], s[44:45], 0, v[158:159]
	v_ashrrev_i32_e32 v147, 31, v146
	v_lshl_add_u64 v[182:183], v[146:147], 2, v[182:183]
	global_store_dwordx4 v[182:183], v[14:17], off offset:512

.LBB0_1447:
	s_andn2_b64 vcc, exec, s[68:69]
	s_cbranch_vccnz .LBB0_1449
	v_ashrrev_i32_e32 v138, 7, v180
	v_add_u32_e32 v182, v138, v181
	v_ashrrev_i32_e32 v183, 31, v182
	v_lshrrev_b32_e32 v147, 6, v146
	v_lshlrev_b64 v[182:183], 8, v[182:183]
	v_and_or_b32 v138, v147, 1, v182
	v_or_b32_e32 v182, v138, v155
	v_lshlrev_b64 v[182:183], 10, v[182:183]
	v_and_or_b32 v138, v146, 60, v182
	v_or_b32_e32 v182, v138, v145
	v_lshl_add_u64 v[182:183], v[182:183], 1, s[46:47]
	global_store_dwordx2 v[182:183], v[168:169], off
	v_lshl_add_u64 v[168:169], s[48:49], 0, v[158:159]
	v_ashrrev_i32_e32 v147, 31, v146
	v_lshl_add_u64 v[168:169], v[146:147], 2, v[168:169]
	global_store_dwordx4 v[168:169], v[14:17], off offset:512

.LBB0_1451:
	v_bfe_u32 v138, v10, 16, 1
	v_add3_u32 v138, v10, v138, s80
	v_bfe_u32 v147, v11, 16, 1
	v_lshrrev_b32_e32 v138, 16, v138
	v_add3_u32 v147, v11, v147, s80
	v_and_or_b32 v168, v147, s81, v138
	v_bfe_u32 v138, v12, 16, 1
	v_add3_u32 v138, v12, v138, s80
	v_bfe_u32 v147, v13, 16, 1
	v_lshrrev_b32_e32 v138, 16, v138
	v_add3_u32 v147, v13, v147, s80
	v_and_or_b32 v169, v147, s81, v138
	s_cmp_lt_i32 s10, 3
	s_cbranch_scc1 .LBB0_1459
	s_cmp_lg_u32 s10, 3
	s_cbranch_scc0 .LBB0_1456
	v_lshlrev_b32_e32 v184, 1, v179
	v_lshl_add_u64 v[182:183], s[50:51], 0, v[160:161]
	v_ashrrev_i32_e32 v185, 31, v184
	v_lshl_add_u64 v[182:183], v[182:183], 0, v[184:185]
	global_store_dwordx2 v[182:183], v[168:169], off
	s_and_saveexec_b64 s[68:69], s[8:9]
	s_cbranch_execz .LBB0_1455
	v_ashrrev_i32_e32 v163, 31, v162
	v_lshlrev_b64 v[162:163], 19, v[162:163]
	v_lshl_add_u64 v[162:163], s[52:53], 0, v[162:163]
	v_lshl_add_u64 v[162:163], v[162:163], 0, v[164:165]
	v_ashrrev_i32_e32 v147, 31, v146
	v_lshl_add_u64 v[162:163], v[146:147], 2, v[162:163]
	global_store_dwordx4 v[162:163], v[10:13], off offset:576

.LBB0_1456:
	s_andn2_b64 vcc, exec, s[68:69]
	s_cbranch_vccnz .LBB0_1458
	v_lshlrev_b32_e32 v162, 1, v179
	v_lshl_add_u64 v[160:161], s[24:25], 0, v[160:161]
	v_ashrrev_i32_e32 v163, 31, v162
	v_lshl_add_u64 v[160:161], v[160:161], 0, v[162:163]
	global_store_dwordx2 v[160:161], v[168:169], off
	v_lshl_add_u64 v[160:161], s[44:45], 0, v[158:159]
	v_ashrrev_i32_e32 v147, 31, v146
	v_lshl_add_u64 v[160:161], v[146:147], 2, v[160:161]
	global_store_dwordx4 v[160:161], v[10:13], off offset:576

.LBB0_1459:
	s_andn2_b64 vcc, exec, s[68:69]
	s_cbranch_vccnz .LBB0_1461
	v_ashrrev_i32_e32 v138, 7, v179
	v_add_u32_e32 v160, v138, v181
	v_ashrrev_i32_e32 v161, 31, v160
	v_lshrrev_b32_e32 v147, 6, v179
	v_lshlrev_b64 v[160:161], 8, v[160:161]
	v_and_or_b32 v138, v147, 1, v160
	v_or_b32_e32 v160, v138, v155
	v_lshlrev_b64 v[160:161], 10, v[160:161]
	v_and_or_b32 v138, v179, 60, v160
	v_or_b32_e32 v160, v138, v145
	v_lshl_add_u64 v[158:159], s[48:49], 0, v[158:159]
	v_ashrrev_i32_e32 v147, 31, v146
	v_lshl_add_u64 v[160:161], v[160:161], 1, s[46:47]
	v_lshl_add_u64 v[158:159], v[146:147], 2, v[158:159]
	global_store_dwordx2 v[160:161], v[168:169], off
	global_store_dwordx4 v[158:159], v[10:13], off offset:576

.LBB0_1462:
	s_and_b64 vcc, exec, s[68:69]
	v_lshl_add_u64 v[166:167], s[54:55], 0, v[158:159]
	s_cbranch_vccz .LBB0_1426
	v_pk_mul_f32 v[182:183], v[46:47], s[56:57] op_sel_hi:[1,0]
	v_pk_mul_f32 v[168:169], v[48:49], s[56:57] op_sel_hi:[1,0]
	v_bfe_u32 v138, v182, 16, 1
	v_add3_u32 v138, v182, v138, s80
	v_bfe_u32 v147, v183, 16, 1
	v_lshrrev_b32_e32 v138, 16, v138
	v_add3_u32 v147, v183, v147, s80
	v_and_or_b32 v182, v147, s81, v138
	v_bfe_u32 v138, v168, 16, 1
	v_add3_u32 v138, v168, v138, s80
	v_bfe_u32 v147, v169, 16, 1
	v_lshrrev_b32_e32 v138, 16, v138
	v_add3_u32 v147, v169, v147, s80
	v_and_or_b32 v183, v147, s81, v138
	v_lshl_add_u64 v[168:169], v[148:149], 1, v[166:167]
	global_store_dwordx2 v[168:169], v[182:183], off
	s_and_b64 vcc, exec, s[6:7]
	s_mov_b64 s[68:69], -1
	s_cbranch_vccz .LBB0_1427
.LBB0_1464:
	s_and_b64 vcc, exec, s[68:69]
	s_cbranch_vccz .LBB0_1438
	v_pk_mul_f32 v[182:183], v[38:39], s[56:57] op_sel_hi:[1,0]
	v_pk_mul_f32 v[168:169], v[40:41], s[56:57] op_sel_hi:[1,0]
	v_bfe_u32 v138, v182, 16, 1
	v_add3_u32 v138, v182, v138, s80
	v_bfe_u32 v147, v183, 16, 1
	v_lshrrev_b32_e32 v138, 16, v138
	v_add3_u32 v147, v183, v147, s80
	v_and_or_b32 v182, v147, s81, v138
	v_bfe_u32 v138, v168, 16, 1
	v_add3_u32 v138, v168, v138, s80
	v_bfe_u32 v147, v169, 16, 1
	v_lshrrev_b32_e32 v138, 16, v138
	v_add3_u32 v147, v169, v147, s80
	v_and_or_b32 v183, v147, s81, v138
	v_lshl_add_u64 v[168:169], v[150:151], 1, v[166:167]
	global_store_dwordx2 v[168:169], v[182:183], off
	s_and_b64 vcc, exec, s[6:7]
	s_mov_b64 s[68:69], -1
	s_cbranch_vccz .LBB0_1439
.LBB0_1466:
	s_and_b64 vcc, exec, s[68:69]
	s_cbranch_vccz .LBB0_1450
	v_pk_mul_f32 v[182:183], v[14:15], s[56:57] op_sel_hi:[1,0]
	v_pk_mul_f32 v[168:169], v[16:17], s[56:57] op_sel_hi:[1,0]
	v_bfe_u32 v138, v182, 16, 1
	v_add3_u32 v138, v182, v138, s80
	v_bfe_u32 v147, v183, 16, 1
	v_lshrrev_b32_e32 v138, 16, v138
	v_add3_u32 v147, v183, v147, s80
	v_and_or_b32 v182, v147, s81, v138
	v_bfe_u32 v138, v168, 16, 1
	v_add3_u32 v138, v168, v138, s80
	v_bfe_u32 v147, v169, 16, 1
	v_lshrrev_b32_e32 v138, 16, v138
	v_add3_u32 v147, v169, v147, s80
	v_and_or_b32 v183, v147, s81, v138
	v_lshl_add_u64 v[168:169], v[152:153], 1, v[166:167]
	global_store_dwordx2 v[168:169], v[182:183], off
	s_and_b64 vcc, exec, s[6:7]
	s_mov_b64 s[68:69], -1
	s_cbranch_vccz .LBB0_1451
.LBB0_1468:
	s_and_b64 vcc, exec, s[68:69]
	s_cbranch_vccz .LBB0_1470
	v_pk_mul_f32 v[160:161], v[10:11], s[56:57] op_sel_hi:[1,0]
	v_pk_mul_f32 v[158:159], v[12:13], s[56:57] op_sel_hi:[1,0]
	v_bfe_u32 v138, v160, 16, 1
	v_add3_u32 v138, v160, v138, s80
	v_bfe_u32 v147, v161, 16, 1
	v_lshrrev_b32_e32 v138, 16, v138
	v_add3_u32 v147, v161, v147, s80
	v_and_or_b32 v160, v147, s81, v138
	v_bfe_u32 v138, v158, 16, 1
	v_add3_u32 v138, v158, v138, s80
	v_bfe_u32 v147, v159, 16, 1
	v_lshrrev_b32_e32 v138, 16, v138
	v_add3_u32 v147, v159, v147, s80
	v_and_or_b32 v161, v147, s81, v138
	v_lshl_add_u64 v[158:159], v[156:157], 1, v[166:167]
	global_store_dwordx2 v[158:159], v[160:161], off
.LBB0_1470:
	v_add_u32_e32 v160, 0xb0, v154
	v_ashrrev_i32_e32 v138, 10, v160
	v_and_b32_e32 v169, -2, v138
	v_lshrrev_b32_e32 v138, 3, v160
	v_and_b32_e32 v168, 0xfe, v138
	v_and_b32_e32 v138, 0x1fff, v160
	v_ashrrev_i32_e32 v161, 31, v160
	v_cmp_lt_u32_e64 s[8:9], s79, v138
	v_add_u32_e32 v138, 0xffffe200, v138
	v_lshlrev_b64 v[158:159], 9, v[160:161]
	v_lshlrev_b64 v[154:155], 10, v[160:161]
	v_ashrrev_i32_e32 v160, 13, v160
	v_lshlrev_b64 v[162:163], 10, v[138:139]
	s_and_b64 vcc, exec, s[6:7]
	s_mov_b64 s[68:69], -1
	s_cbranch_vccnz .LBB0_1518
	v_bfe_u32 v138, v30, 16, 1
	v_add3_u32 v138, v30, v138, s80
	v_bfe_u32 v147, v31, 16, 1
	v_lshrrev_b32_e32 v138, 16, v138
	v_add3_u32 v147, v31, v147, s80
	v_and_or_b32 v164, v147, s81, v138
	v_bfe_u32 v138, v32, 16, 1
	v_add3_u32 v138, v32, v138, s80
	v_bfe_u32 v147, v33, 16, 1
	v_lshrrev_b32_e32 v138, 16, v138
	v_add3_u32 v147, v33, v147, s80
	v_and_or_b32 v165, v147, s81, v138
	s_cmp_lt_i32 s10, 3
	s_cbranch_scc1 .LBB0_1479
	v_lshlrev_b32_e32 v166, 1, v146
	s_cmp_lg_u32 s10, 3
	v_ashrrev_i32_e32 v167, 31, v166
	s_cbranch_scc0 .LBB0_1476
	v_lshl_add_u64 v[182:183], s[50:51], 0, v[158:159]
	v_lshl_add_u64 v[182:183], v[182:183], 0, v[166:167]
	global_store_dwordx2 v[182:183], v[164:165], off
	s_and_saveexec_b64 s[68:69], s[8:9]
	s_cbranch_execz .LBB0_1475
	v_ashrrev_i32_e32 v161, 31, v160
	v_lshlrev_b64 v[182:183], 19, v[160:161]
	v_lshl_add_u64 v[182:183], s[52:53], 0, v[182:183]
	v_lshl_add_u64 v[182:183], v[182:183], 0, v[162:163]
	v_ashrrev_i32_e32 v147, 31, v146
	v_lshl_add_u64 v[182:183], v[146:147], 2, v[182:183]
	global_store_dwordx4 v[182:183], v[30:33], off

.LBB0_1476:
	s_andn2_b64 vcc, exec, s[68:69]
	s_cbranch_vccnz .LBB0_1478
	v_lshl_add_u64 v[182:183], s[24:25], 0, v[158:159]
	v_lshl_add_u64 v[166:167], v[182:183], 0, v[166:167]
	global_store_dwordx2 v[166:167], v[164:165], off
	v_lshl_add_u64 v[166:167], s[44:45], 0, v[154:155]
	v_ashrrev_i32_e32 v147, 31, v146
	v_lshl_add_u64 v[166:167], v[146:147], 2, v[166:167]
	global_store_dwordx4 v[166:167], v[30:33], off

.LBB0_1479:
	s_andn2_b64 vcc, exec, s[68:69]
	s_cbranch_vccnz .LBB0_1481
	v_ashrrev_i32_e32 v138, 7, v146
	v_add_u32_e32 v166, v169, v138
	v_ashrrev_i32_e32 v167, 31, v166
	v_lshrrev_b32_e32 v147, 6, v146
	v_lshlrev_b64 v[166:167], 8, v[166:167]
	v_and_or_b32 v138, v147, 1, v166
	v_or_b32_e32 v166, v138, v168
	v_lshlrev_b64 v[166:167], 10, v[166:167]
	v_and_or_b32 v138, v146, 60, v166
	v_or_b32_e32 v166, v138, v145
	v_lshl_add_u64 v[166:167], v[166:167], 1, s[46:47]
	global_store_dwordx2 v[166:167], v[164:165], off
	v_lshl_add_u64 v[164:165], s[48:49], 0, v[154:155]
	v_ashrrev_i32_e32 v147, 31, v146
	v_lshl_add_u64 v[164:165], v[146:147], 2, v[164:165]
	global_store_dwordx4 v[164:165], v[30:33], off

.LBB0_1483:
	v_bfe_u32 v138, v22, 16, 1
	v_add3_u32 v138, v22, v138, s80
	v_bfe_u32 v147, v23, 16, 1
	v_lshrrev_b32_e32 v138, 16, v138
	v_add3_u32 v147, v23, v147, s80
	v_and_or_b32 v148, v147, s81, v138
	v_bfe_u32 v138, v24, 16, 1
	v_add3_u32 v138, v24, v138, s80
	v_bfe_u32 v147, v25, 16, 1
	v_lshrrev_b32_e32 v138, 16, v138
	v_add3_u32 v147, v25, v147, s80
	v_and_or_b32 v149, v147, s81, v138
	s_cmp_lt_i32 s10, 3
	s_cbranch_scc1 .LBB0_1491
	v_lshlrev_b32_e32 v166, 1, v178
	s_cmp_lg_u32 s10, 3
	v_ashrrev_i32_e32 v167, 31, v166
	s_cbranch_scc0 .LBB0_1488
	v_lshl_add_u64 v[182:183], s[50:51], 0, v[158:159]
	v_lshl_add_u64 v[182:183], v[182:183], 0, v[166:167]
	global_store_dwordx2 v[182:183], v[148:149], off
	s_and_saveexec_b64 s[68:69], s[8:9]
	s_cbranch_execz .LBB0_1487
	v_ashrrev_i32_e32 v161, 31, v160
	v_lshlrev_b64 v[182:183], 19, v[160:161]
	v_lshl_add_u64 v[182:183], s[52:53], 0, v[182:183]
	v_lshl_add_u64 v[182:183], v[182:183], 0, v[162:163]
	v_ashrrev_i32_e32 v147, 31, v146
	v_lshl_add_u64 v[182:183], v[146:147], 2, v[182:183]
	global_store_dwordx4 v[182:183], v[22:25], off offset:64

.LBB0_1488:
	s_andn2_b64 vcc, exec, s[68:69]
	s_cbranch_vccnz .LBB0_1490
	v_lshl_add_u64 v[182:183], s[24:25], 0, v[158:159]
	v_lshl_add_u64 v[166:167], v[182:183], 0, v[166:167]
	global_store_dwordx2 v[166:167], v[148:149], off
	v_lshl_add_u64 v[166:167], s[44:45], 0, v[154:155]
	v_ashrrev_i32_e32 v147, 31, v146
	v_lshl_add_u64 v[166:167], v[146:147], 2, v[166:167]
	global_store_dwordx4 v[166:167], v[22:25], off offset:64

.LBB0_1491:
	s_andn2_b64 vcc, exec, s[68:69]
	s_cbranch_vccnz .LBB0_1493
	v_ashrrev_i32_e32 v138, 7, v178
	v_add_u32_e32 v166, v138, v169
	v_ashrrev_i32_e32 v167, 31, v166
	v_lshrrev_b32_e32 v147, 6, v178
	v_lshlrev_b64 v[166:167], 8, v[166:167]
	v_and_or_b32 v138, v147, 1, v166
	v_or_b32_e32 v166, v138, v168
	v_lshlrev_b64 v[166:167], 10, v[166:167]
	v_and_or_b32 v138, v178, 60, v166
	v_or_b32_e32 v166, v138, v145
	v_lshl_add_u64 v[166:167], v[166:167], 1, s[46:47]
	global_store_dwordx2 v[166:167], v[148:149], off
	v_lshl_add_u64 v[148:149], s[48:49], 0, v[154:155]
	v_ashrrev_i32_e32 v147, 31, v146
	v_lshl_add_u64 v[148:149], v[146:147], 2, v[148:149]
	global_store_dwordx4 v[148:149], v[22:25], off offset:64

.LBB0_1495:
	v_bfe_u32 v138, v6, 16, 1
	v_add3_u32 v138, v6, v138, s80
	v_bfe_u32 v147, v7, 16, 1
	v_lshrrev_b32_e32 v138, 16, v138
	v_add3_u32 v147, v7, v147, s80
	v_and_or_b32 v148, v147, s81, v138
	v_bfe_u32 v138, v8, 16, 1
	v_add3_u32 v138, v8, v138, s80
	v_bfe_u32 v147, v9, 16, 1
	v_lshrrev_b32_e32 v138, 16, v138
	v_add3_u32 v147, v9, v147, s80
	v_and_or_b32 v149, v147, s81, v138
	s_cmp_lt_i32 s10, 3
	s_cbranch_scc1 .LBB0_1503
	v_lshlrev_b32_e32 v150, 1, v180
	s_cmp_lg_u32 s10, 3
	v_ashrrev_i32_e32 v151, 31, v150
	s_cbranch_scc0 .LBB0_1500
	v_lshl_add_u64 v[166:167], s[50:51], 0, v[158:159]
	v_lshl_add_u64 v[166:167], v[166:167], 0, v[150:151]
	global_store_dwordx2 v[166:167], v[148:149], off
	s_and_saveexec_b64 s[68:69], s[8:9]
	s_cbranch_execz .LBB0_1499
	v_ashrrev_i32_e32 v161, 31, v160
	v_lshlrev_b64 v[166:167], 19, v[160:161]
	v_lshl_add_u64 v[166:167], s[52:53], 0, v[166:167]
	v_lshl_add_u64 v[166:167], v[166:167], 0, v[162:163]
	v_ashrrev_i32_e32 v147, 31, v146
	v_lshl_add_u64 v[166:167], v[146:147], 2, v[166:167]
	global_store_dwordx4 v[166:167], v[6:9], off offset:512

.LBB0_1500:
	s_andn2_b64 vcc, exec, s[68:69]
	s_cbranch_vccnz .LBB0_1502
	v_lshl_add_u64 v[166:167], s[24:25], 0, v[158:159]
	v_lshl_add_u64 v[150:151], v[166:167], 0, v[150:151]
	global_store_dwordx2 v[150:151], v[148:149], off
	v_lshl_add_u64 v[150:151], s[44:45], 0, v[154:155]
	v_ashrrev_i32_e32 v147, 31, v146
	v_lshl_add_u64 v[150:151], v[146:147], 2, v[150:151]
	global_store_dwordx4 v[150:151], v[6:9], off offset:512

.LBB0_1503:
	s_andn2_b64 vcc, exec, s[68:69]
	s_cbranch_vccnz .LBB0_1505
	v_ashrrev_i32_e32 v138, 7, v180
	v_add_u32_e32 v150, v138, v169
	v_ashrrev_i32_e32 v151, 31, v150
	v_lshrrev_b32_e32 v147, 6, v146
	v_lshlrev_b64 v[150:151], 8, v[150:151]
	v_and_or_b32 v138, v147, 1, v150
	v_or_b32_e32 v150, v138, v168
	v_lshlrev_b64 v[150:151], 10, v[150:151]
	v_and_or_b32 v138, v146, 60, v150
	v_or_b32_e32 v150, v138, v145
	v_lshl_add_u64 v[150:151], v[150:151], 1, s[46:47]
	global_store_dwordx2 v[150:151], v[148:149], off
	v_lshl_add_u64 v[148:149], s[48:49], 0, v[154:155]
	v_ashrrev_i32_e32 v147, 31, v146
	v_lshl_add_u64 v[148:149], v[146:147], 2, v[148:149]
	global_store_dwordx4 v[148:149], v[6:9], off offset:512

.LBB0_1507:
	v_bfe_u32 v138, v2, 16, 1
	v_add3_u32 v138, v2, v138, s80
	v_bfe_u32 v147, v3, 16, 1
	v_lshrrev_b32_e32 v138, 16, v138
	v_add3_u32 v147, v3, v147, s80
	v_and_or_b32 v148, v147, s81, v138
	v_bfe_u32 v138, v4, 16, 1
	v_add3_u32 v138, v4, v138, s80
	v_bfe_u32 v147, v5, 16, 1
	v_lshrrev_b32_e32 v138, 16, v138
	v_add3_u32 v147, v5, v147, s80
	v_and_or_b32 v149, v147, s81, v138
	s_cmp_lt_i32 s10, 3
	s_cbranch_scc1 .LBB0_1515
	v_lshlrev_b32_e32 v150, 1, v179
	s_cmp_lg_u32 s10, 3
	v_ashrrev_i32_e32 v151, 31, v150
	s_cbranch_scc0 .LBB0_1512
	v_lshl_add_u64 v[152:153], s[50:51], 0, v[158:159]
	v_lshl_add_u64 v[152:153], v[152:153], 0, v[150:151]
	global_store_dwordx2 v[152:153], v[148:149], off
	s_and_saveexec_b64 s[6:7], s[8:9]
	s_cbranch_execz .LBB0_1511
	v_ashrrev_i32_e32 v161, 31, v160
	v_lshlrev_b64 v[152:153], 19, v[160:161]
	v_lshl_add_u64 v[152:153], s[52:53], 0, v[152:153]
	v_lshl_add_u64 v[152:153], v[152:153], 0, v[162:163]
	v_ashrrev_i32_e32 v147, 31, v146
	v_lshl_add_u64 v[152:153], v[146:147], 2, v[152:153]
	global_store_dwordx4 v[152:153], v[2:5], off offset:576

.LBB0_1512:
	s_andn2_b64 vcc, exec, s[6:7]
	s_cbranch_vccnz .LBB0_1514
	v_lshl_add_u64 v[152:153], s[24:25], 0, v[158:159]
	v_lshl_add_u64 v[150:151], v[152:153], 0, v[150:151]
	global_store_dwordx2 v[150:151], v[148:149], off
	v_lshl_add_u64 v[150:151], s[44:45], 0, v[154:155]
	v_ashrrev_i32_e32 v147, 31, v146
	v_lshl_add_u64 v[150:151], v[146:147], 2, v[150:151]
	global_store_dwordx4 v[150:151], v[2:5], off offset:576

.LBB0_1515:
	s_andn2_b64 vcc, exec, s[6:7]
	s_cbranch_vccnz .LBB0_1517
	v_ashrrev_i32_e32 v138, 7, v179
	v_add_u32_e32 v150, v138, v169
	v_ashrrev_i32_e32 v151, 31, v150
	v_lshrrev_b32_e32 v147, 6, v179
	v_lshlrev_b64 v[150:151], 8, v[150:151]
	v_and_or_b32 v138, v147, 1, v150
	v_or_b32_e32 v150, v138, v168
	v_lshlrev_b64 v[150:151], 10, v[150:151]
	v_and_or_b32 v138, v179, 60, v150
	v_or_b32_e32 v150, v138, v145
	v_lshl_add_u64 v[150:151], v[150:151], 1, s[46:47]
	global_store_dwordx2 v[150:151], v[148:149], off
	v_lshl_add_u64 v[148:149], s[48:49], 0, v[154:155]
	v_ashrrev_i32_e32 v147, 31, v146
	v_lshl_add_u64 v[146:147], v[146:147], 2, v[148:149]
	global_store_dwordx4 v[146:147], v[2:5], off offset:576

.LBB0_1518:
	s_and_b64 vcc, exec, s[68:69]
	v_lshl_add_u64 v[164:165], s[54:55], 0, v[154:155]
	s_cbranch_vccz .LBB0_1482
	v_pk_mul_f32 v[182:183], v[30:31], s[56:57] op_sel_hi:[1,0]
	v_pk_mul_f32 v[166:167], v[32:33], s[56:57] op_sel_hi:[1,0]
	v_bfe_u32 v138, v182, 16, 1
	v_add3_u32 v138, v182, v138, s80
	v_bfe_u32 v147, v183, 16, 1
	v_lshrrev_b32_e32 v138, 16, v138
	v_add3_u32 v147, v183, v147, s80
	v_and_or_b32 v182, v147, s81, v138
	v_bfe_u32 v138, v166, 16, 1
	v_add3_u32 v138, v166, v138, s80
	v_bfe_u32 v147, v167, 16, 1
	v_lshrrev_b32_e32 v138, 16, v138
	v_add3_u32 v147, v167, v147, s80
	v_and_or_b32 v183, v147, s81, v138
	v_lshl_add_u64 v[148:149], v[148:149], 1, v[164:165]
	global_store_dwordx2 v[148:149], v[182:183], off
	s_and_b64 vcc, exec, s[6:7]
	s_mov_b64 s[68:69], -1
	s_cbranch_vccz .LBB0_1483
.LBB0_1520:
	s_and_b64 vcc, exec, s[68:69]
	s_cbranch_vccz .LBB0_1494
	v_pk_mul_f32 v[166:167], v[22:23], s[56:57] op_sel_hi:[1,0]
	v_pk_mul_f32 v[148:149], v[24:25], s[56:57] op_sel_hi:[1,0]
	v_bfe_u32 v138, v166, 16, 1
	v_add3_u32 v138, v166, v138, s80
	v_bfe_u32 v147, v167, 16, 1
	v_lshrrev_b32_e32 v138, 16, v138
	v_add3_u32 v147, v167, v147, s80
	v_and_or_b32 v166, v147, s81, v138
	v_bfe_u32 v138, v148, 16, 1
	v_add3_u32 v138, v148, v138, s80
	v_bfe_u32 v147, v149, 16, 1
	v_lshrrev_b32_e32 v138, 16, v138
	v_add3_u32 v147, v149, v147, s80
	v_and_or_b32 v167, v147, s81, v138
	v_lshl_add_u64 v[148:149], v[150:151], 1, v[164:165]
	global_store_dwordx2 v[148:149], v[166:167], off
	s_and_b64 vcc, exec, s[6:7]
	s_mov_b64 s[68:69], -1
	s_cbranch_vccz .LBB0_1495
.LBB0_1522:
	s_and_b64 vcc, exec, s[68:69]
	s_cbranch_vccz .LBB0_1506
	v_pk_mul_f32 v[150:151], v[6:7], s[56:57] op_sel_hi:[1,0]
	v_pk_mul_f32 v[148:149], v[8:9], s[56:57] op_sel_hi:[1,0]
	v_bfe_u32 v138, v150, 16, 1
	v_add3_u32 v138, v150, v138, s80
	v_bfe_u32 v147, v151, 16, 1
	v_lshrrev_b32_e32 v138, 16, v138
	v_add3_u32 v147, v151, v147, s80
	v_and_or_b32 v150, v147, s81, v138
	v_bfe_u32 v138, v148, 16, 1
	v_add3_u32 v138, v148, v138, s80
	v_bfe_u32 v147, v149, 16, 1
	v_lshrrev_b32_e32 v138, 16, v138
	v_add3_u32 v147, v149, v147, s80
	v_and_or_b32 v151, v147, s81, v138
	v_lshl_add_u64 v[148:149], v[152:153], 1, v[164:165]
	global_store_dwordx2 v[148:149], v[150:151], off
	s_and_b64 vcc, exec, s[6:7]
	s_mov_b64 s[6:7], -1
	s_cbranch_vccz .LBB0_1507
.LBB0_1524:
	s_and_b64 vcc, exec, s[6:7]
	s_cbranch_vccz .LBB0_1526
	v_pk_mul_f32 v[148:149], v[2:3], s[56:57] op_sel_hi:[1,0]
	v_pk_mul_f32 v[146:147], v[4:5], s[56:57] op_sel_hi:[1,0]
	v_bfe_u32 v138, v148, 16, 1
	v_add3_u32 v138, v148, v138, s80
	v_bfe_u32 v145, v149, 16, 1
	v_lshrrev_b32_e32 v138, 16, v138
	v_add3_u32 v145, v149, v145, s80
	v_and_or_b32 v148, v145, s81, v138
	v_bfe_u32 v138, v146, 16, 1
	v_add3_u32 v138, v146, v138, s80
	v_bfe_u32 v145, v147, 16, 1
	v_lshrrev_b32_e32 v138, 16, v138
	v_add3_u32 v145, v147, v145, s80
	v_and_or_b32 v149, v145, s81, v138
	v_lshl_add_u64 v[146:147], v[156:157], 1, v[164:165]
	global_store_dwordx2 v[146:147], v[148:149], off

.LBB0_1587:
	s_nop 0
	v_lshl_add_u64 v[12:13], s[14:15], 0, v[2:3]
	v_add_co_u32_e32 v14, vcc, 0x16000000, v12
	v_lshl_add_u64 v[16:17], s[8:9], 0, v[2:3]
	s_nop 0
	v_addc_co_u32_e32 v15, vcc, 0, v13, vcc
	v_add_co_u32_e32 v12, vcc, 0x16001000, v12
	global_load_dwordx4 v[4:7], v[14:15], off offset:2048
	global_load_dwordx4 v[8:11], v[14:15], off offset:3072
	v_addc_co_u32_e32 v13, vcc, 0, v13, vcc
	global_load_dwordx4 v[12:15], v[12:13], off
	s_add_i32 s12, s12, s6
	s_add_u32 s8, s8, s10
	v_add_co_u32_e32 v18, vcc, 0x8300000, v16
	s_addc_u32 s9, s9, s11
	s_nop 0
	v_addc_co_u32_e32 v19, vcc, 0, v17, vcc
	s_add_u32 s14, s14, s2
	v_add_co_u32_e32 v20, vcc, 0x8340000, v16
	s_addc_u32 s15, s15, s3
	s_nop 0
	v_addc_co_u32_e32 v21, vcc, 0, v17, vcc
	v_add_co_u32_e32 v16, vcc, 0x8380000, v16
	s_cmpk_lt_i32 s12, 0x80
	s_nop 0
	v_addc_co_u32_e32 v17, vcc, 0, v17, vcc
	s_waitcnt vmcnt(0) lgkmcnt(0)
	global_store_dwordx4 v[18:19], v[4:7], off
	global_store_dwordx4 v[20:21], v[8:11], off
	global_store_dwordx4 v[16:17], v[12:15], off
	s_cbranch_scc1 .LBB0_1587

.LBB0_1589:
	s_lshl_b32 s5, s20, 2
	v_add_u32_e32 v132, s27, v138
	s_add_u32 s6, s34, s5
	v_ashrrev_i32_e32 v133, 31, v132
	s_addc_u32 s7, s35, 0
	v_lshlrev_b64 v[132:133], 10, v[132:133]
	v_lshl_add_u64 v[132:133], s[6:7], 0, v[132:133]
	v_mov_b32_e32 v131, v179
	v_lshl_add_u64 v[132:133], v[132:133], 0, v[130:131]
	v_readlane_b32 s5, v228, 29
	global_store_dwordx4 v[132:133], v[126:129], off
	global_store_dwordx4 v[132:133], v[122:125], off offset:64
	global_store_dwordx4 v[132:133], v[110:113], off offset:512
	global_store_dwordx4 v[132:133], v[102:105], off offset:576
	s_nop 1
	v_add_u32_e32 v102, s5, v138
	v_ashrrev_i32_e32 v103, 31, v102
	v_lshlrev_b64 v[102:103], 10, v[102:103]
	v_lshl_add_u64 v[102:103], s[6:7], 0, v[102:103]
	v_lshl_add_u64 v[102:103], v[102:103], 0, v[130:131]
	global_store_dwordx4 v[102:103], v[118:121], off
	global_store_dwordx4 v[102:103], v[114:117], off offset:64
	global_store_dwordx4 v[102:103], v[94:97], off offset:512
	global_store_dwordx4 v[102:103], v[86:89], off offset:576
	s_nop 1
	v_add_u32_e32 v86, s45, v138
	v_ashrrev_i32_e32 v87, 31, v86
	v_lshlrev_b64 v[86:87], 10, v[86:87]
	v_lshl_add_u64 v[86:87], s[6:7], 0, v[86:87]
	v_lshl_add_u64 v[86:87], v[86:87], 0, v[130:131]
	global_store_dwordx4 v[86:87], v[106:109], off
	global_store_dwordx4 v[86:87], v[98:101], off offset:64
	global_store_dwordx4 v[86:87], v[78:81], off offset:512
	global_store_dwordx4 v[86:87], v[74:77], off offset:576
	s_nop 1
	v_add_u32_e32 v74, s2, v138
	v_ashrrev_i32_e32 v75, 31, v74
	v_lshlrev_b64 v[74:75], 10, v[74:75]
	v_lshl_add_u64 v[74:75], s[6:7], 0, v[74:75]
	v_lshl_add_u64 v[74:75], v[74:75], 0, v[130:131]
	global_store_dwordx4 v[74:75], v[90:93], off
	global_store_dwordx4 v[74:75], v[82:85], off offset:64
	global_store_dwordx4 v[74:75], v[70:73], off offset:512
	global_store_dwordx4 v[74:75], v[66:69], off offset:576
	s_nop 1
	v_add_u32_e32 v66, s3, v138
	v_ashrrev_i32_e32 v67, 31, v66
	v_lshlrev_b64 v[66:67], 10, v[66:67]
	v_lshl_add_u64 v[66:67], s[6:7], 0, v[66:67]
	v_lshl_add_u64 v[66:67], v[66:67], 0, v[130:131]
	global_store_dwordx4 v[66:67], v[62:65], off
	global_store_dwordx4 v[66:67], v[58:61], off offset:64
	global_store_dwordx4 v[66:67], v[46:49], off offset:512
	global_store_dwordx4 v[66:67], v[38:41], off offset:576
	s_nop 1
	v_add_u32_e32 v38, s49, v138
	v_ashrrev_i32_e32 v39, 31, v38
	v_lshlrev_b64 v[38:39], 10, v[38:39]
	v_lshl_add_u64 v[38:39], s[6:7], 0, v[38:39]
	v_lshl_add_u64 v[38:39], v[38:39], 0, v[130:131]
	global_store_dwordx4 v[38:39], v[54:57], off
	global_store_dwordx4 v[38:39], v[50:53], off offset:64
	global_store_dwordx4 v[38:39], v[30:33], off offset:512
	global_store_dwordx4 v[38:39], v[22:25], off offset:576
	s_nop 1
	v_add_u32_e32 v22, s52, v138
	v_ashrrev_i32_e32 v23, 31, v22
	v_lshlrev_b64 v[22:23], 10, v[22:23]
	v_lshl_add_u64 v[22:23], s[6:7], 0, v[22:23]
	v_lshl_add_u64 v[22:23], v[22:23], 0, v[130:131]
	global_store_dwordx4 v[22:23], v[42:45], off
	global_store_dwordx4 v[22:23], v[34:37], off offset:64
	global_store_dwordx4 v[22:23], v[14:17], off offset:512
	global_store_dwordx4 v[22:23], v[10:13], off offset:576
	s_nop 1
	v_add_u32_e32 v10, s53, v138
	v_ashrrev_i32_e32 v11, 31, v10
	v_lshlrev_b64 v[10:11], 10, v[10:11]
	v_lshl_add_u64 v[10:11], s[6:7], 0, v[10:11]
	v_lshl_add_u64 v[10:11], v[10:11], 0, v[130:131]
	global_store_dwordx4 v[10:11], v[26:29], off
	global_store_dwordx4 v[10:11], v[18:21], off offset:64
	global_store_dwordx4 v[10:11], v[6:9], off offset:512
	global_store_dwordx4 v[10:11], v[2:5], off offset:576
	s_waitcnt vmcnt(0)
	s_barrier

.LBB0_1591:
	v_mov_b32_e32 v180, v0
	s_mov_b64 s[6:7], -1
	v_readfirstlane_b32 s22, v180
	s_ashr_i32 s10, s22, 6
	v_and_b32_e32 v182, 63, v180
	s_cmp_lg_u32 s5, s33
	s_cbranch_scc0 .LBB0_1597
	s_waitcnt lgkmcnt(0)
	v_mov_b64_e32 v[2:3], s[0:1]
	global_load_dwordx2 v[4:5], v[2:3], off offset:64 sc0 sc1
	s_waitcnt vmcnt(0)
	global_load_dwordx2 v[8:9], v[2:3], off offset:32 sc0 sc1
	s_waitcnt vmcnt(0)
	v_ashrrev_i32_e32 v41, 5, v180
	v_lshlrev_b32_e32 v2, 14, v41
	v_and_b32_e32 v178, 0x1c000, v2
	s_mov_b32 s83, s57
	v_lshlrev_b32_e32 v40, 4, v180
	v_and_b32_e32 v6, 0xf0, v40
	v_mov_b32_e32 v7, v179
	s_lshl_b32 s5, s10, 5
	s_and_b32 s6, s5, 0xffffffc0
	s_lshl_b32 s5, s10, 7
	v_and_b32_e32 v203, 31, v180
	s_and_b32 s11, s5, 0x80
	s_mov_b32 s5, 0x20000
	v_lshrrev_b32_e32 v181, 5, v182
	s_mov_b64 s[8:9], 0
	s_waitcnt lgkmcnt(0)
	v_lshl_add_u64 v[26:27], s[54:55], 2, v[4:5]
	v_lshl_add_u64 v[2:3], v[8:9], 0, v[178:179]
	v_lshl_add_u64 v[4:5], v[2:3], 0, s[82:83]
	v_and_b32_e32 v2, 0x100, v40
	v_mov_b32_e32 v3, v179
	v_lshl_add_u64 v[10:11], v[4:5], 0, v[2:3]
	v_ashrrev_i32_e32 v4, 8, v180
	v_ashrrev_i32_e32 v5, 31, v4
	v_lshl_add_u64 v[4:5], v[4:5], 2, v[26:27]
	global_load_dword v4, v[4:5], off
	v_add_u32_e32 v3, 16, v41
	v_lshl_add_u64 v[8:9], v[8:9], 0, s[76:77]
	s_waitcnt vmcnt(0)
	v_ashrrev_i32_e32 v5, 31, v4
	v_lshlrev_b64 v[4:5], 17, v[4:5]
	v_lshl_add_u64 v[12:13], v[10:11], 0, v[4:5]
	v_lshl_add_u64 v[18:19], v[12:13], 0, v[6:7]
	v_ashrrev_i32_e32 v12, 3, v3
	v_ashrrev_i32_e32 v13, 31, v12
	v_lshl_add_u64 v[12:13], v[12:13], 2, v[26:27]
	global_load_dword v12, v[12:13], off
	v_add_u32_e32 v3, 32, v41
	v_or_b32_e32 v4, v4, v178
	v_or3_b32 v4, v4, v2, v6
	v_lshl_add_u64 v[200:201], v[8:9], 0, v[4:5]
	s_waitcnt vmcnt(0)
	v_ashrrev_i32_e32 v13, 31, v12
	v_lshlrev_b64 v[12:13], 17, v[12:13]
	v_lshl_add_u64 v[14:15], v[10:11], 0, v[12:13]
	v_lshl_add_u64 v[22:23], v[14:15], 0, v[6:7]
	v_ashrrev_i32_e32 v14, 3, v3
	v_ashrrev_i32_e32 v15, 31, v14
	v_lshl_add_u64 v[14:15], v[14:15], 2, v[26:27]
	global_load_dword v14, v[14:15], off
	v_add_u32_e32 v3, 48, v41
	v_or_b32_e32 v12, v12, v178
	v_or3_b32 v12, v12, v2, v6
	v_lshl_add_u64 v[198:199], v[8:9], 0, v[12:13]
	s_waitcnt vmcnt(0)
	v_ashrrev_i32_e32 v15, 31, v14
	v_lshlrev_b64 v[14:15], 17, v[14:15]
	v_lshl_add_u64 v[16:17], v[10:11], 0, v[14:15]
	v_lshl_add_u64 v[28:29], v[16:17], 0, v[6:7]
	v_ashrrev_i32_e32 v16, 3, v3
	v_ashrrev_i32_e32 v17, 31, v16
	v_lshl_add_u64 v[16:17], v[16:17], 2, v[26:27]
	global_load_dword v16, v[16:17], off
	v_add_u32_e32 v3, 64, v41
	v_or_b32_e32 v14, v14, v178
	v_or3_b32 v14, v14, v2, v6
	v_lshl_add_u64 v[196:197], v[8:9], 0, v[14:15]
	s_waitcnt vmcnt(0)
	v_ashrrev_i32_e32 v17, 31, v16
	v_lshlrev_b64 v[16:17], 17, v[16:17]
	v_lshl_add_u64 v[20:21], v[10:11], 0, v[16:17]
	v_lshl_add_u64 v[32:33], v[20:21], 0, v[6:7]
	v_ashrrev_i32_e32 v20, 3, v3
	v_ashrrev_i32_e32 v21, 31, v20
	v_lshl_add_u64 v[20:21], v[20:21], 2, v[26:27]
	global_load_dword v20, v[20:21], off
	v_add_u32_e32 v3, 0x50, v41
	v_or_b32_e32 v16, v16, v178
	v_or3_b32 v16, v16, v2, v6
	v_lshl_add_u64 v[194:195], v[8:9], 0, v[16:17]
	s_waitcnt vmcnt(0)
	v_ashrrev_i32_e32 v21, 31, v20
	v_lshlrev_b64 v[20:21], 17, v[20:21]
	v_lshl_add_u64 v[24:25], v[10:11], 0, v[20:21]
	v_lshl_add_u64 v[34:35], v[24:25], 0, v[6:7]
	v_ashrrev_i32_e32 v24, 3, v3
	v_ashrrev_i32_e32 v25, 31, v24
	v_lshl_add_u64 v[24:25], v[24:25], 2, v[26:27]
	global_load_dword v24, v[24:25], off
	v_add_u32_e32 v3, 0x60, v41
	v_or_b32_e32 v20, v20, v178
	v_or3_b32 v20, v20, v2, v6
	v_lshl_add_u64 v[192:193], v[8:9], 0, v[20:21]
	s_waitcnt vmcnt(0)
	v_ashrrev_i32_e32 v25, 31, v24
	v_lshlrev_b64 v[24:25], 17, v[24:25]
	v_lshl_add_u64 v[30:31], v[10:11], 0, v[24:25]
	v_lshl_add_u64 v[36:37], v[30:31], 0, v[6:7]
	v_ashrrev_i32_e32 v30, 3, v3
	v_add_u32_e32 v3, 0x70, v41
	v_ashrrev_i32_e32 v42, 3, v3
	v_ashrrev_i32_e32 v31, 31, v30
	v_ashrrev_i32_e32 v43, 31, v42
	v_lshl_add_u64 v[30:31], v[30:31], 2, v[26:27]
	v_lshl_add_u64 v[26:27], v[42:43], 2, v[26:27]
	global_load_dword v30, v[30:31], off
	v_lshrrev_b32_e32 v3, 4, v180
	global_load_dword v26, v[26:27], off
	v_mul_lo_u32 v41, v3, s48
	v_lshlrev_b32_e32 v3, 3, v180
	v_and_b32_e32 v48, 0x78, v3
	v_or_b32_e32 v3, s6, v203
	s_waitcnt vmcnt(1)
	v_ashrrev_i32_e32 v31, 31, v30
	v_lshlrev_b64 v[30:31], 17, v[30:31]
	s_waitcnt vmcnt(0)
	v_ashrrev_i32_e32 v27, 31, v26
	v_lshlrev_b64 v[26:27], 17, v[26:27]
	v_lshl_add_u64 v[38:39], v[10:11], 0, v[30:31]
	v_lshl_add_u64 v[10:11], v[10:11], 0, v[26:27]
	v_lshl_add_u64 v[42:43], v[10:11], 0, v[6:7]
	v_ashrrev_i32_e32 v10, 3, v180
	v_ashrrev_i32_e32 v11, 31, v10
	v_lshl_add_u64 v[38:39], v[38:39], 0, v[6:7]
	v_lshlrev_b64 v[44:45], 11, v[10:11]
	v_or_b32_e32 v7, s11, v203
	v_mov_b32_e32 v11, s96
	v_lshl_add_u64 v[46:47], s[58:59], 0, v[44:45]
	v_mul_lo_u32 v49, v10, s48
	v_and_b32_e32 v10, 0x70, v40
	v_mad_u32_u24 v7, v7, s48, v11
	v_mov_b32_e32 v11, v179
	global_load_dwordx4 v[130:133], v[18:19], off nt
	global_load_dwordx4 v[134:137], v[22:23], off nt
	global_load_dwordx4 v[138:141], v[28:29], off nt
	global_load_dwordx4 v[142:145], v[32:33], off nt
	global_load_dwordx4 v[146:149], v[34:35], off nt
	global_load_dwordx4 v[150:153], v[36:37], off nt
	global_load_dwordx4 v[154:157], v[38:39], off nt
	global_load_dwordx4 v[158:161], v[42:43], off nt
	v_lshl_add_u64 v[22:23], v[46:47], 0, v[10:11]
	v_add_co_u32_e32 v28, vcc, s5, v22
	s_mov_b32 s5, 0x40000
	s_nop 0
	v_addc_co_u32_e32 v29, vcc, 0, v23, vcc
	global_load_dwordx4 v[162:165], v[22:23], off
	global_load_dwordx4 v[166:169], v[28:29], off
	v_add_co_u32_e32 v28, vcc, s5, v22
	s_mov_b32 s5, 0x60000
	s_nop 0
	v_addc_co_u32_e32 v29, vcc, 0, v23, vcc
	v_add_co_u32_e32 v22, vcc, s5, v22
	global_load_dwordx4 v[170:173], v[28:29], off
	s_nop 0
	v_addc_co_u32_e32 v23, vcc, 0, v23, vcc
	global_load_dwordx4 v[174:177], v[22:23], off
	v_or_b32_e32 v22, v26, v178
	v_or3_b32 v26, v22, v2, v6
	v_or_b32_e32 v22, v30, v178
	v_mul_lo_u32 v40, v3, s48
	v_or3_b32 v30, v22, v2, v6
	v_or_b32_e32 v22, v24, v178
	v_lshlrev_b32_e32 v3, 4, v181
	v_add_u32_e32 v19, s96, v41
	v_add_u32_e32 v11, s96, v49
	v_add_u32_e32 v18, s96, v40
	v_or_b32_e32 v44, v44, v10
	v_or3_b32 v24, v22, v2, v6
	v_mov_b32_e32 v2, 0
	v_lshl_add_u64 v[184:185], s[74:75], 0, v[44:45]
	v_lshl_add_u64 v[186:187], v[8:9], 0, v[26:27]
	v_lshl_add_u64 v[188:189], v[8:9], 0, v[30:31]
	v_lshl_add_u64 v[190:191], v[8:9], 0, v[24:25]
	v_add_u32_e32 v178, v19, v48
	v_add_u32_e32 v204, v11, v10
	v_add_u32_e32 v205, v18, v3
	v_add_u32_e32 v206, v7, v3
	v_mov_b32_e32 v3, v2
	v_mov_b32_e32 v4, v2
	v_mov_b32_e32 v5, v2
	v_mov_b32_e32 v6, v2
	v_mov_b32_e32 v7, v2
	v_mov_b32_e32 v8, v2
	v_mov_b32_e32 v9, v2
	v_mov_b32_e32 v10, v2
	v_mov_b32_e32 v11, v2
	v_mov_b32_e32 v12, v2
	v_mov_b32_e32 v13, v2
	v_mov_b32_e32 v14, v2
	v_mov_b32_e32 v15, v2
	v_mov_b32_e32 v16, v2
	v_mov_b32_e32 v17, v2
	v_mov_b32_e32 v18, v2
	v_mov_b32_e32 v19, v2
	v_mov_b32_e32 v20, v2
	v_mov_b32_e32 v21, v2
	v_mov_b32_e32 v22, v2
	v_mov_b32_e32 v23, v2
	v_mov_b32_e32 v24, v2
	v_mov_b32_e32 v25, v2
	v_mov_b32_e32 v26, v2
	v_mov_b32_e32 v27, v2
	v_mov_b32_e32 v28, v2
	v_mov_b32_e32 v29, v2
	v_mov_b32_e32 v30, v2
	v_mov_b32_e32 v31, v2
	v_mov_b32_e32 v32, v2
	v_mov_b32_e32 v33, v2
	v_mov_b32_e32 v34, v2
	v_mov_b32_e32 v35, v2
	v_mov_b32_e32 v36, v2
	v_mov_b32_e32 v37, v2
	v_mov_b32_e32 v38, v2
	v_mov_b32_e32 v39, v2
	v_mov_b32_e32 v40, v2
	v_mov_b32_e32 v41, v2
	v_mov_b32_e32 v42, v2
	v_mov_b32_e32 v43, v2
	v_mov_b32_e32 v44, v2
	v_mov_b32_e32 v45, v2
	v_mov_b32_e32 v46, v2
	v_mov_b32_e32 v47, v2
	v_mov_b32_e32 v48, v2
	v_mov_b32_e32 v49, v2
	v_mov_b32_e32 v50, v2
	v_mov_b32_e32 v51, v2
	v_mov_b32_e32 v52, v2
	v_mov_b32_e32 v53, v2
	v_mov_b32_e32 v54, v2
	v_mov_b32_e32 v55, v2
	v_mov_b32_e32 v56, v2
	v_mov_b32_e32 v57, v2
	v_mov_b32_e32 v58, v2
	v_mov_b32_e32 v59, v2
	v_mov_b32_e32 v60, v2
	v_mov_b32_e32 v61, v2
	v_mov_b32_e32 v62, v2
	v_mov_b32_e32 v63, v2
	v_mov_b32_e32 v64, v2
	v_mov_b32_e32 v65, v2
	v_mov_b32_e32 v66, v2
	v_mov_b32_e32 v67, v2
	v_mov_b32_e32 v68, v2
	v_mov_b32_e32 v69, v2
	v_mov_b32_e32 v70, v2
	v_mov_b32_e32 v71, v2
	v_mov_b32_e32 v72, v2
	v_mov_b32_e32 v73, v2
	v_mov_b32_e32 v74, v2
	v_mov_b32_e32 v75, v2
	v_mov_b32_e32 v76, v2
	v_mov_b32_e32 v77, v2
	v_mov_b32_e32 v78, v2
	v_mov_b32_e32 v79, v2
	v_mov_b32_e32 v80, v2
	v_mov_b32_e32 v81, v2
	v_mov_b32_e32 v82, v2
	v_mov_b32_e32 v83, v2
	v_mov_b32_e32 v84, v2
	v_mov_b32_e32 v85, v2
	v_mov_b32_e32 v86, v2
	v_mov_b32_e32 v87, v2
	v_mov_b32_e32 v88, v2
	v_mov_b32_e32 v89, v2
	v_mov_b32_e32 v90, v2
	v_mov_b32_e32 v91, v2
	v_mov_b32_e32 v92, v2
	v_mov_b32_e32 v93, v2
	v_mov_b32_e32 v94, v2
	v_mov_b32_e32 v95, v2
	v_mov_b32_e32 v96, v2
	v_mov_b32_e32 v97, v2
	v_mov_b32_e32 v98, v2
	v_mov_b32_e32 v99, v2
	v_mov_b32_e32 v100, v2
	v_mov_b32_e32 v101, v2
	v_mov_b32_e32 v102, v2
	v_mov_b32_e32 v103, v2
	v_mov_b32_e32 v104, v2
	v_mov_b32_e32 v105, v2
	v_mov_b32_e32 v106, v2
	v_mov_b32_e32 v107, v2
	v_mov_b32_e32 v108, v2
	v_mov_b32_e32 v109, v2
	v_mov_b32_e32 v110, v2
	v_mov_b32_e32 v111, v2
	v_mov_b32_e32 v112, v2
	v_mov_b32_e32 v113, v2
	v_mov_b32_e32 v114, v2
	v_mov_b32_e32 v115, v2
	v_mov_b32_e32 v116, v2
	v_mov_b32_e32 v117, v2
	v_mov_b32_e32 v118, v2
	v_mov_b32_e32 v119, v2
	v_mov_b32_e32 v120, v2
	v_mov_b32_e32 v121, v2
	v_mov_b32_e32 v122, v2
	v_mov_b32_e32 v123, v2
	v_mov_b32_e32 v124, v2
	v_mov_b32_e32 v125, v2
	v_mov_b32_e32 v126, v2
	v_mov_b32_e32 v127, v2
	v_mov_b32_e32 v128, v2
	v_mov_b32_e32 v129, v2
	s_branch .LBB0_1594

.LBB0_1594:
	s_waitcnt vmcnt(0)
	v_bfe_u32 v207, v130, 16, 1
	v_add3_u32 v207, v130, v207, s28
	v_bfe_u32 v208, v131, 16, 1
	v_lshrrev_b32_e32 v207, 16, v207
	v_add3_u32 v208, v131, v208, s28
	v_and_or_b32 v208, v208, s29, v207
	v_bfe_u32 v207, v132, 16, 1
	v_add3_u32 v207, v132, v207, s28
	v_bfe_u32 v209, v133, 16, 1
	v_lshrrev_b32_e32 v207, 16, v207
	v_add3_u32 v209, v133, v209, s28
	v_and_or_b32 v209, v209, s29, v207
	v_bfe_u32 v207, v134, 16, 1
	v_add3_u32 v207, v134, v207, s28
	v_bfe_u32 v210, v135, 16, 1
	v_lshrrev_b32_e32 v207, 16, v207
	v_add3_u32 v210, v135, v210, s28
	v_and_or_b32 v210, v210, s29, v207
	v_bfe_u32 v207, v136, 16, 1
	v_add3_u32 v207, v136, v207, s28
	v_bfe_u32 v211, v137, 16, 1
	v_lshrrev_b32_e32 v207, 16, v207
	v_add3_u32 v211, v137, v211, s28
	v_and_or_b32 v211, v211, s29, v207
	v_bfe_u32 v207, v138, 16, 1
	s_waitcnt lgkmcnt(0)
	s_barrier
	ds_write2st64_b64 v178, v[208:209], v[210:211] offset1:9
	v_add3_u32 v207, v138, v207, s28
	v_bfe_u32 v208, v139, 16, 1
	v_lshrrev_b32_e32 v207, 16, v207
	v_add3_u32 v208, v139, v208, s28
	v_and_or_b32 v208, v208, s29, v207
	v_bfe_u32 v207, v140, 16, 1
	v_add3_u32 v207, v140, v207, s28
	v_bfe_u32 v209, v141, 16, 1
	v_lshrrev_b32_e32 v207, 16, v207
	v_add3_u32 v209, v141, v209, s28
	v_and_or_b32 v209, v209, s29, v207
	v_bfe_u32 v207, v142, 16, 1
	v_add3_u32 v207, v142, v207, s28
	v_bfe_u32 v210, v143, 16, 1
	v_lshrrev_b32_e32 v207, 16, v207
	v_add3_u32 v210, v143, v210, s28
	v_and_or_b32 v210, v210, s29, v207
	v_bfe_u32 v207, v144, 16, 1
	v_add3_u32 v207, v144, v207, s28
	v_bfe_u32 v211, v145, 16, 1
	v_lshrrev_b32_e32 v207, 16, v207
	v_add3_u32 v211, v145, v211, s28
	v_and_or_b32 v211, v211, s29, v207
	v_bfe_u32 v207, v146, 16, 1
	ds_write2st64_b64 v178, v[208:209], v[210:211] offset0:18 offset1:27
	v_add3_u32 v207, v146, v207, s28
	v_bfe_u32 v208, v147, 16, 1
	v_lshrrev_b32_e32 v207, 16, v207
	v_add3_u32 v208, v147, v208, s28
	v_and_or_b32 v208, v208, s29, v207
	v_bfe_u32 v207, v148, 16, 1
	v_add3_u32 v207, v148, v207, s28
	v_bfe_u32 v209, v149, 16, 1
	v_lshrrev_b32_e32 v207, 16, v207
	v_add3_u32 v209, v149, v209, s28
	v_and_or_b32 v209, v209, s29, v207
	v_bfe_u32 v207, v150, 16, 1
	v_add3_u32 v207, v150, v207, s28
	v_bfe_u32 v210, v151, 16, 1
	v_lshrrev_b32_e32 v207, 16, v207
	v_add3_u32 v210, v151, v210, s28
	v_and_or_b32 v210, v210, s29, v207
	v_bfe_u32 v207, v152, 16, 1
	v_add3_u32 v207, v152, v207, s28
	v_bfe_u32 v211, v153, 16, 1
	v_lshrrev_b32_e32 v207, 16, v207
	v_add3_u32 v211, v153, v211, s28
	v_and_or_b32 v211, v211, s29, v207
	v_bfe_u32 v207, v154, 16, 1
	ds_write2st64_b64 v178, v[208:209], v[210:211] offset0:36 offset1:45
	v_add3_u32 v207, v154, v207, s28
	v_bfe_u32 v208, v155, 16, 1
	v_lshrrev_b32_e32 v207, 16, v207
	v_add3_u32 v208, v155, v208, s28
	v_and_or_b32 v208, v208, s29, v207
	v_bfe_u32 v207, v156, 16, 1
	v_add3_u32 v207, v156, v207, s28
	v_bfe_u32 v209, v157, 16, 1
	v_lshrrev_b32_e32 v207, 16, v207
	v_add3_u32 v209, v157, v209, s28
	v_and_or_b32 v209, v209, s29, v207
	v_bfe_u32 v207, v158, 16, 1
	v_add3_u32 v207, v158, v207, s28
	v_bfe_u32 v210, v159, 16, 1
	v_lshrrev_b32_e32 v207, 16, v207
	v_add3_u32 v210, v159, v210, s28
	v_and_or_b32 v210, v210, s29, v207
	v_bfe_u32 v207, v160, 16, 1
	v_add3_u32 v207, v160, v207, s28
	v_bfe_u32 v211, v161, 16, 1
	v_lshrrev_b32_e32 v207, 16, v207
	v_add3_u32 v211, v161, v211, s28
	v_and_or_b32 v211, v211, s29, v207
	s_cmpk_eq_i32 s8, 0x3c00
	ds_write2st64_b64 v178, v[208:209], v[210:211] offset0:54 offset1:63
	ds_write_b128 v204, v[162:165] offset:36864
	ds_write_b128 v204, v[166:169] offset:46080
	ds_write_b128 v204, v[170:173] offset:55296
	ds_write_b128 v204, v[174:177] offset:64512
	s_waitcnt lgkmcnt(0)
	s_barrier
	s_cbranch_scc1 .LBB0_1593
	v_add_co_u32_e32 v162, vcc, 0xfffa0000, v184
	v_lshl_add_u64 v[130:131], v[200:201], 0, s[8:9]
	s_nop 0
	v_addc_co_u32_e32 v163, vcc, -1, v185, vcc
	v_add_co_u32_e32 v166, vcc, 0xfffc0000, v184
	v_lshl_add_u64 v[134:135], v[198:199], 0, s[8:9]
	s_nop 0
	v_addc_co_u32_e32 v167, vcc, -1, v185, vcc
	v_add_co_u32_e32 v170, vcc, 0xfffe0000, v184
	v_lshl_add_u64 v[138:139], v[196:197], 0, s[8:9]
	v_lshl_add_u64 v[142:143], v[194:195], 0, s[8:9]
	v_lshl_add_u64 v[146:147], v[192:193], 0, s[8:9]
	v_lshl_add_u64 v[150:151], v[190:191], 0, s[8:9]
	v_lshl_add_u64 v[154:155], v[188:189], 0, s[8:9]
	v_lshl_add_u64 v[158:159], v[186:187], 0, s[8:9]
	v_addc_co_u32_e32 v171, vcc, -1, v185, vcc
	global_load_dwordx4 v[130:133], v[130:131], off nt
	s_nop 0
	global_load_dwordx4 v[134:137], v[134:135], off nt
	s_nop 0
	global_load_dwordx4 v[138:141], v[138:139], off nt
	s_nop 0
	global_load_dwordx4 v[142:145], v[142:143], off nt
	s_nop 0
	global_load_dwordx4 v[146:149], v[146:147], off nt
	s_nop 0
	global_load_dwordx4 v[150:153], v[150:151], off nt
	s_nop 0
	global_load_dwordx4 v[154:157], v[154:155], off nt
	s_nop 0
	global_load_dwordx4 v[158:161], v[158:159], off nt
	s_nop 0
	global_load_dwordx4 v[162:165], v[162:163], off
	s_nop 0
	global_load_dwordx4 v[166:169], v[166:167], off
	s_nop 0
	global_load_dwordx4 v[170:173], v[170:171], off
	s_nop 0
	global_load_dwordx4 v[174:177], v[184:185], off
	s_branch .LBB0_1593
.LBB0_1596:
	s_ashr_i32 s7, s6, 31
	s_lshl_b64 s[6:7], s[6:7], 10
	s_add_u32 s5, s36, s6
	s_addc_u32 s7, s92, s7
	s_lshl_b32 s6, s11, 2
	s_add_u32 s6, s5, s6
	s_addc_u32 s7, s7, 0
	v_lshlrev_b32_e32 v178, 2, v203
	s_waitcnt vmcnt(0)
	v_lshl_add_u64 v[130:131], s[6:7], 0, v[178:179]
	v_lshlrev_b32_e32 v178, 12, v181
	v_lshl_add_u64 v[132:133], v[130:131], 0, v[178:179]
	global_store_dword v[132:133], v114, off
	global_store_dword v[132:133], v115, off offset:1024
	global_store_dword v[132:133], v116, off offset:2048
	global_store_dword v[132:133], v117, off offset:3072
	v_or_b32_e32 v114, 0x2000, v178
	v_mov_b32_e32 v115, v179
	v_lshl_add_u64 v[116:117], v[130:131], 0, v[114:115]
	global_store_dword v[116:117], v118, off
	v_or_b32_e32 v116, 0x2400, v178
	v_mov_b32_e32 v117, v179
	v_lshl_add_u64 v[134:135], v[130:131], 0, v[116:117]
	global_store_dword v[134:135], v119, off
	v_or_b32_e32 v118, 0x2800, v178
	v_mov_b32_e32 v119, v179
	v_lshl_add_u64 v[134:135], v[130:131], 0, v[118:119]
	global_store_dword v[134:135], v120, off
	v_or_b32_e32 v134, 0x2c00, v178
	v_mov_b32_e32 v135, v179
	v_lshl_add_u64 v[136:137], v[130:131], 0, v[134:135]
	global_store_dword v[136:137], v121, off
	v_or_b32_e32 v120, 0x4000, v178
	v_mov_b32_e32 v121, v179
	v_lshl_add_u64 v[136:137], v[130:131], 0, v[120:121]
	global_store_dword v[136:137], v122, off
	v_or_b32_e32 v136, 0x4400, v178
	v_mov_b32_e32 v137, v179
	v_lshl_add_u64 v[138:139], v[130:131], 0, v[136:137]
	global_store_dword v[138:139], v123, off
	v_or_b32_e32 v122, 0x4800, v178
	v_mov_b32_e32 v123, v179
	v_lshl_add_u64 v[138:139], v[130:131], 0, v[122:123]
	global_store_dword v[138:139], v124, off
	v_or_b32_e32 v138, 0x4c00, v178
	v_mov_b32_e32 v139, v179
	v_lshl_add_u64 v[140:141], v[130:131], 0, v[138:139]
	global_store_dword v[140:141], v125, off
	v_or_b32_e32 v124, 0x6000, v178
	v_mov_b32_e32 v125, v179
	v_lshl_add_u64 v[140:141], v[130:131], 0, v[124:125]
	global_store_dword v[140:141], v126, off
	v_or_b32_e32 v140, 0x6400, v178
	v_mov_b32_e32 v141, v179
	v_lshl_add_u64 v[142:143], v[130:131], 0, v[140:141]
	global_store_dword v[142:143], v127, off
	v_or_b32_e32 v126, 0x6800, v178
	v_mov_b32_e32 v127, v179
	v_lshl_add_u64 v[142:143], v[130:131], 0, v[126:127]
	global_store_dword v[142:143], v128, off
	v_or_b32_e32 v142, 0x6c00, v178
	v_mov_b32_e32 v143, v179
	v_lshl_add_u64 v[144:145], v[130:131], 0, v[142:143]
	global_store_dword v[144:145], v129, off
	v_lshl_add_u64 v[128:129], v[130:131], 0, s[84:85]
	global_store_dword v[132:133], v98, off offset:128
	global_store_dword v[132:133], v99, off offset:1152
	global_store_dword v[132:133], v100, off offset:2176
	global_store_dword v[132:133], v101, off offset:3200
	v_lshl_add_u64 v[98:99], v[128:129], 0, v[114:115]
	global_store_dword v[98:99], v102, off
	v_lshl_add_u64 v[98:99], v[128:129], 0, v[116:117]
	global_store_dword v[98:99], v103, off
	v_lshl_add_u64 v[98:99], v[128:129], 0, v[118:119]
	global_store_dword v[98:99], v104, off
	v_lshl_add_u64 v[98:99], v[128:129], 0, v[134:135]
	global_store_dword v[98:99], v105, off
	v_lshl_add_u64 v[98:99], v[128:129], 0, v[120:121]
	global_store_dword v[98:99], v106, off
	v_lshl_add_u64 v[98:99], v[128:129], 0, v[136:137]
	global_store_dword v[98:99], v107, off
	v_lshl_add_u64 v[98:99], v[128:129], 0, v[122:123]
	global_store_dword v[98:99], v108, off
	v_lshl_add_u64 v[98:99], v[128:129], 0, v[138:139]
	global_store_dword v[98:99], v109, off
	v_lshl_add_u64 v[98:99], v[128:129], 0, v[124:125]
	global_store_dword v[98:99], v110, off
	v_lshl_add_u64 v[98:99], v[128:129], 0, v[140:141]
	global_store_dword v[98:99], v111, off
	v_lshl_add_u64 v[98:99], v[128:129], 0, v[126:127]
	global_store_dword v[98:99], v112, off
	v_lshl_add_u64 v[98:99], v[128:129], 0, v[142:143]
	s_mov_b64 s[6:7], 0x100
	global_store_dword v[98:99], v113, off
	v_lshl_add_u64 v[98:99], v[130:131], 0, s[6:7]
	global_store_dword v[132:133], v82, off offset:256
	global_store_dword v[132:133], v83, off offset:1280
	global_store_dword v[132:133], v84, off offset:2304
	global_store_dword v[132:133], v85, off offset:3328
	v_lshl_add_u64 v[82:83], v[98:99], 0, v[114:115]
	global_store_dword v[82:83], v86, off
	v_lshl_add_u64 v[82:83], v[98:99], 0, v[116:117]
	global_store_dword v[82:83], v87, off
	v_lshl_add_u64 v[82:83], v[98:99], 0, v[118:119]
	global_store_dword v[82:83], v88, off
	v_lshl_add_u64 v[82:83], v[98:99], 0, v[134:135]
	global_store_dword v[82:83], v89, off
	v_lshl_add_u64 v[82:83], v[98:99], 0, v[120:121]
	global_store_dword v[82:83], v90, off
	v_lshl_add_u64 v[82:83], v[98:99], 0, v[136:137]
	global_store_dword v[82:83], v91, off
	v_lshl_add_u64 v[82:83], v[98:99], 0, v[122:123]
	global_store_dword v[82:83], v92, off
	v_lshl_add_u64 v[82:83], v[98:99], 0, v[138:139]
	global_store_dword v[82:83], v93, off
	v_lshl_add_u64 v[82:83], v[98:99], 0, v[124:125]
	global_store_dword v[82:83], v94, off
	v_lshl_add_u64 v[82:83], v[98:99], 0, v[140:141]
	global_store_dword v[82:83], v95, off
	v_lshl_add_u64 v[82:83], v[98:99], 0, v[126:127]
	global_store_dword v[82:83], v96, off
	v_lshl_add_u64 v[82:83], v[98:99], 0, v[142:143]
	s_mov_b64 s[6:7], 0x180
	global_store_dword v[82:83], v97, off
	v_lshl_add_u64 v[82:83], v[130:131], 0, s[6:7]
	global_store_dword v[132:133], v66, off offset:384
	global_store_dword v[132:133], v67, off offset:1408
	global_store_dword v[132:133], v68, off offset:2432
	global_store_dword v[132:133], v69, off offset:3456
	v_lshl_add_u64 v[66:67], v[82:83], 0, v[114:115]
	global_store_dword v[66:67], v70, off
	v_lshl_add_u64 v[66:67], v[82:83], 0, v[116:117]
	global_store_dword v[66:67], v71, off
	v_lshl_add_u64 v[66:67], v[82:83], 0, v[118:119]
	global_store_dword v[66:67], v72, off
	v_lshl_add_u64 v[66:67], v[82:83], 0, v[134:135]
	global_store_dword v[66:67], v73, off
	v_lshl_add_u64 v[66:67], v[82:83], 0, v[120:121]
	global_store_dword v[66:67], v74, off
	v_lshl_add_u64 v[66:67], v[82:83], 0, v[136:137]
	global_store_dword v[66:67], v75, off
	v_lshl_add_u64 v[66:67], v[82:83], 0, v[122:123]
	global_store_dword v[66:67], v76, off
	v_lshl_add_u64 v[66:67], v[82:83], 0, v[138:139]
	global_store_dword v[66:67], v77, off
	v_lshl_add_u64 v[66:67], v[82:83], 0, v[124:125]
	global_store_dword v[66:67], v78, off
	v_lshl_add_u64 v[66:67], v[82:83], 0, v[140:141]
	global_store_dword v[66:67], v79, off
	v_lshl_add_u64 v[66:67], v[82:83], 0, v[126:127]
	global_store_dword v[66:67], v80, off
	v_lshl_add_u64 v[66:67], v[82:83], 0, v[142:143]
	global_store_dword v[66:67], v81, off
	v_or_b32_e32 v66, 0x8000, v178
	v_mov_b32_e32 v67, v179
	v_lshl_add_u64 v[68:69], v[130:131], 0, v[66:67]
	global_store_dword v[68:69], v50, off
	v_or_b32_e32 v68, 0x8400, v178
	v_mov_b32_e32 v69, v179
	v_lshl_add_u64 v[70:71], v[130:131], 0, v[68:69]
	global_store_dword v[70:71], v51, off
	v_or_b32_e32 v50, 0x8800, v178
	v_mov_b32_e32 v51, v179
	v_lshl_add_u64 v[70:71], v[130:131], 0, v[50:51]
	global_store_dword v[70:71], v52, off
	v_or_b32_e32 v70, 0x8c00, v178
	v_mov_b32_e32 v71, v179
	v_lshl_add_u64 v[72:73], v[130:131], 0, v[70:71]
	global_store_dword v[72:73], v53, off
	v_or_b32_e32 v52, 0xa000, v178
	v_mov_b32_e32 v53, v179
	v_lshl_add_u64 v[72:73], v[130:131], 0, v[52:53]
	global_store_dword v[72:73], v54, off
	v_or_b32_e32 v72, 0xa400, v178
	v_mov_b32_e32 v73, v179
	v_lshl_add_u64 v[74:75], v[130:131], 0, v[72:73]
	global_store_dword v[74:75], v55, off
	v_or_b32_e32 v54, 0xa800, v178
	v_mov_b32_e32 v55, v179
	v_lshl_add_u64 v[74:75], v[130:131], 0, v[54:55]
	global_store_dword v[74:75], v56, off
	v_or_b32_e32 v74, 0xac00, v178
	v_mov_b32_e32 v75, v179
	v_lshl_add_u64 v[76:77], v[130:131], 0, v[74:75]
	global_store_dword v[76:77], v57, off
	v_or_b32_e32 v56, 0xc000, v178
	v_mov_b32_e32 v57, v179
	v_lshl_add_u64 v[76:77], v[130:131], 0, v[56:57]
	global_store_dword v[76:77], v58, off
	v_or_b32_e32 v76, 0xc400, v178
	v_mov_b32_e32 v77, v179
	v_lshl_add_u64 v[78:79], v[130:131], 0, v[76:77]
	global_store_dword v[78:79], v59, off
	v_or_b32_e32 v58, 0xc800, v178
	v_mov_b32_e32 v59, v179
	v_lshl_add_u64 v[78:79], v[130:131], 0, v[58:59]
	global_store_dword v[78:79], v60, off
	v_or_b32_e32 v78, 0xcc00, v178
	v_mov_b32_e32 v79, v179
	v_lshl_add_u64 v[80:81], v[130:131], 0, v[78:79]
	global_store_dword v[80:81], v61, off
	v_or_b32_e32 v60, 0xe000, v178
	v_mov_b32_e32 v61, v179
	v_lshl_add_u64 v[80:81], v[130:131], 0, v[60:61]
	global_store_dword v[80:81], v62, off
	v_or_b32_e32 v80, 0xe400, v178
	v_mov_b32_e32 v81, v179
	v_lshl_add_u64 v[84:85], v[130:131], 0, v[80:81]
	global_store_dword v[84:85], v63, off
	v_or_b32_e32 v62, 0xe800, v178
	v_mov_b32_e32 v63, v179
	v_lshl_add_u64 v[84:85], v[130:131], 0, v[62:63]
	v_or_b32_e32 v178, 0xec00, v178
	global_store_dword v[84:85], v64, off
	v_lshl_add_u64 v[84:85], v[130:131], 0, v[178:179]
	global_store_dword v[84:85], v65, off
	v_lshl_add_u64 v[64:65], v[128:129], 0, v[66:67]
	global_store_dword v[64:65], v34, off
	v_lshl_add_u64 v[64:65], v[128:129], 0, v[68:69]
	global_store_dword v[64:65], v35, off
	v_lshl_add_u64 v[34:35], v[128:129], 0, v[50:51]
	global_store_dword v[34:35], v36, off
	v_lshl_add_u64 v[34:35], v[128:129], 0, v[70:71]
	global_store_dword v[34:35], v37, off
	v_lshl_add_u64 v[34:35], v[128:129], 0, v[52:53]
	global_store_dword v[34:35], v38, off
	v_lshl_add_u64 v[34:35], v[128:129], 0, v[72:73]
	global_store_dword v[34:35], v39, off
	v_lshl_add_u64 v[34:35], v[128:129], 0, v[54:55]
	global_store_dword v[34:35], v40, off
	v_lshl_add_u64 v[34:35], v[128:129], 0, v[74:75]
	global_store_dword v[34:35], v41, off
	v_lshl_add_u64 v[34:35], v[128:129], 0, v[56:57]
	global_store_dword v[34:35], v42, off
	v_lshl_add_u64 v[34:35], v[128:129], 0, v[76:77]
	global_store_dword v[34:35], v43, off
	v_lshl_add_u64 v[34:35], v[128:129], 0, v[58:59]
	global_store_dword v[34:35], v44, off
	v_lshl_add_u64 v[34:35], v[128:129], 0, v[78:79]
	global_store_dword v[34:35], v45, off
	v_lshl_add_u64 v[34:35], v[128:129], 0, v[60:61]
	global_store_dword v[34:35], v46, off
	v_lshl_add_u64 v[34:35], v[128:129], 0, v[80:81]
	global_store_dword v[34:35], v47, off
	v_lshl_add_u64 v[34:35], v[128:129], 0, v[62:63]
	global_store_dword v[34:35], v48, off
	v_lshl_add_u64 v[34:35], v[128:129], 0, v[178:179]
	global_store_dword v[34:35], v49, off
	v_lshl_add_u64 v[34:35], v[98:99], 0, v[66:67]
	global_store_dword v[34:35], v18, off
	v_lshl_add_u64 v[34:35], v[98:99], 0, v[68:69]
	global_store_dword v[34:35], v19, off
	v_lshl_add_u64 v[18:19], v[98:99], 0, v[50:51]
	global_store_dword v[18:19], v20, off
	v_lshl_add_u64 v[18:19], v[98:99], 0, v[70:71]
	global_store_dword v[18:19], v21, off
	v_lshl_add_u64 v[18:19], v[98:99], 0, v[52:53]
	global_store_dword v[18:19], v22, off
	v_lshl_add_u64 v[18:19], v[98:99], 0, v[72:73]
	global_store_dword v[18:19], v23, off
	v_lshl_add_u64 v[18:19], v[98:99], 0, v[54:55]
	global_store_dword v[18:19], v24, off
	v_lshl_add_u64 v[18:19], v[98:99], 0, v[74:75]
	global_store_dword v[18:19], v25, off
	v_lshl_add_u64 v[18:19], v[98:99], 0, v[56:57]
	global_store_dword v[18:19], v26, off
	v_lshl_add_u64 v[18:19], v[98:99], 0, v[76:77]
	global_store_dword v[18:19], v27, off
	v_lshl_add_u64 v[18:19], v[98:99], 0, v[58:59]
	global_store_dword v[18:19], v28, off
	v_lshl_add_u64 v[18:19], v[98:99], 0, v[78:79]
	global_store_dword v[18:19], v29, off
	v_lshl_add_u64 v[18:19], v[98:99], 0, v[60:61]
	global_store_dword v[18:19], v30, off
	v_lshl_add_u64 v[18:19], v[98:99], 0, v[80:81]
	global_store_dword v[18:19], v31, off
	v_lshl_add_u64 v[18:19], v[98:99], 0, v[62:63]
	global_store_dword v[18:19], v32, off
	v_lshl_add_u64 v[18:19], v[98:99], 0, v[178:179]
	global_store_dword v[18:19], v33, off
	v_lshl_add_u64 v[18:19], v[82:83], 0, v[66:67]
	global_store_dword v[18:19], v2, off
	v_lshl_add_u64 v[18:19], v[82:83], 0, v[68:69]
	global_store_dword v[18:19], v3, off
	v_lshl_add_u64 v[2:3], v[82:83], 0, v[50:51]
	global_store_dword v[2:3], v4, off
	v_lshl_add_u64 v[2:3], v[82:83], 0, v[70:71]
	global_store_dword v[2:3], v5, off
	v_lshl_add_u64 v[2:3], v[82:83], 0, v[52:53]
	global_store_dword v[2:3], v6, off
	v_lshl_add_u64 v[2:3], v[82:83], 0, v[72:73]
	global_store_dword v[2:3], v7, off
	v_lshl_add_u64 v[2:3], v[82:83], 0, v[54:55]
	global_store_dword v[2:3], v8, off
	v_lshl_add_u64 v[2:3], v[82:83], 0, v[74:75]
	global_store_dword v[2:3], v9, off
	v_lshl_add_u64 v[2:3], v[82:83], 0, v[56:57]
	global_store_dword v[2:3], v10, off
	v_lshl_add_u64 v[2:3], v[82:83], 0, v[76:77]
	global_store_dword v[2:3], v11, off
	v_lshl_add_u64 v[2:3], v[82:83], 0, v[58:59]
	global_store_dword v[2:3], v12, off
	v_lshl_add_u64 v[2:3], v[82:83], 0, v[78:79]
	global_store_dword v[2:3], v13, off
	v_lshl_add_u64 v[2:3], v[82:83], 0, v[60:61]
	global_store_dword v[2:3], v14, off
	v_lshl_add_u64 v[2:3], v[82:83], 0, v[80:81]
	global_store_dword v[2:3], v15, off
	v_lshl_add_u64 v[2:3], v[82:83], 0, v[62:63]
	global_store_dword v[2:3], v16, off
	v_lshl_add_u64 v[2:3], v[82:83], 0, v[178:179]
	s_mov_b64 s[6:7], 0
	global_store_dword v[2:3], v17, off
	s_waitcnt lgkmcnt(0)
	s_barrier

.LBB0_1602:
	s_lshl_b32 s24, s86, 4
	s_lshl_b32 s25, s86, 6
	s_and_b32 s24, s24, 0xffffe000
	s_and_b32 s25, s25, 0x1fc0
	s_or_b32 s90, s24, s25
	s_bfe_u32 s87, s86, 0x20007
	v_add_u32_e32 v2, s90, v35
	v_mov_b64_e32 v[10:11], s[46:47]
	v_mad_i64_i32 v[2:3], s[24:25], v2, s62, v[10:11]
	s_lshl_b32 s56, s87, 8
	v_lshl_add_u64 v[2:3], v[2:3], 0, s[56:57]
	v_lshlrev_b32_e32 v178, 2, v182
	v_add_u32_e32 v4, s90, v36
	v_lshl_add_u64 v[2:3], v[2:3], 0, v[178:179]
	v_mad_i64_i32 v[4:5], s[24:25], v4, s62, v[10:11]
	v_add_co_u32_e32 v2, vcc, s50, v2
	v_lshl_add_u64 v[4:5], v[4:5], 0, s[56:57]
	v_add_u32_e32 v6, s90, v37
	v_addc_co_u32_e32 v3, vcc, 0, v3, vcc
	v_lshl_add_u64 v[4:5], v[4:5], 0, v[178:179]
	v_mad_i64_i32 v[6:7], s[24:25], v6, s62, v[10:11]
	v_add_co_u32_e32 v4, vcc, s50, v4
	v_lshl_add_u64 v[6:7], v[6:7], 0, s[56:57]
	v_add_u32_e32 v8, s90, v38
	v_addc_co_u32_e32 v5, vcc, 0, v5, vcc
	v_lshl_add_u64 v[6:7], v[6:7], 0, v[178:179]
	v_mad_i64_i32 v[8:9], s[24:25], v8, s62, v[10:11]
	v_add_co_u32_e32 v6, vcc, s50, v6
	v_lshl_add_u64 v[8:9], v[8:9], 0, s[56:57]
	v_add_u32_e32 v12, s90, v39
	v_addc_co_u32_e32 v7, vcc, 0, v7, vcc
	v_lshl_add_u64 v[8:9], v[8:9], 0, v[178:179]
	v_mad_i64_i32 v[12:13], s[24:25], v12, s62, v[10:11]
	v_add_co_u32_e32 v8, vcc, s50, v8
	v_lshl_add_u64 v[12:13], v[12:13], 0, s[56:57]
	v_add_u32_e32 v14, s90, v40
	v_addc_co_u32_e32 v9, vcc, 0, v9, vcc
	v_lshl_add_u64 v[12:13], v[12:13], 0, v[178:179]
	v_mad_i64_i32 v[14:15], s[24:25], v14, s62, v[10:11]
	v_add_co_u32_e32 v12, vcc, s50, v12
	v_lshl_add_u64 v[14:15], v[14:15], 0, s[56:57]
	v_add_u32_e32 v16, s90, v41
	v_addc_co_u32_e32 v13, vcc, 0, v13, vcc
	v_lshl_add_u64 v[14:15], v[14:15], 0, v[178:179]
	v_mad_i64_i32 v[16:17], s[24:25], v16, s62, v[10:11]
	v_add_co_u32_e32 v14, vcc, s50, v14
	v_lshl_add_u64 v[16:17], v[16:17], 0, s[56:57]
	v_add_u32_e32 v29, s90, v42
	v_addc_co_u32_e32 v15, vcc, 0, v15, vcc
	v_lshl_add_u64 v[16:17], v[16:17], 0, v[178:179]
	v_mad_i64_i32 v[66:67], s[24:25], v29, s62, v[10:11]
	v_add_co_u32_e32 v16, vcc, s50, v16
	v_lshl_add_u64 v[66:67], v[66:67], 0, s[56:57]
	s_nop 0
	v_addc_co_u32_e32 v17, vcc, 0, v17, vcc
	v_lshl_add_u64 v[66:67], v[66:67], 0, v[178:179]
	v_add_co_u32_e32 v74, vcc, s50, v66
	s_lshl_b32 s56, s87, 9
	s_nop 0
	v_addc_co_u32_e32 v75, vcc, 0, v67, vcc
	global_load_dword v72, v[2:3], off offset:2144
	global_load_dword v71, v[4:5], off offset:2144
	global_load_dword v70, v[6:7], off offset:2144
	global_load_dword v69, v[8:9], off offset:2144
	global_load_dword v68, v[12:13], off offset:2144
	global_load_dword v67, v[14:15], off offset:2144
	global_load_dword v66, v[16:17], off offset:2144
	global_load_dword v65, v[74:75], off offset:2144
	v_add_u32_e32 v2, s90, v44
	v_mad_i64_i32 v[2:3], s[24:25], v2, s62, v[10:11]
	v_lshl_add_u64 v[2:3], v[2:3], 0, s[56:57]
	v_mov_b32_e32 v29, v179
	v_add_u32_e32 v4, s90, v45
	v_lshl_add_u64 v[2:3], v[2:3], 0, v[28:29]
	v_mad_i64_i32 v[4:5], s[24:25], v4, s62, v[10:11]
	v_add_co_u32_e32 v2, vcc, s50, v2
	v_lshl_add_u64 v[4:5], v[4:5], 0, s[56:57]
	v_add_u32_e32 v12, s90, v46
	v_addc_co_u32_e32 v3, vcc, 0, v3, vcc
	v_lshl_add_u64 v[4:5], v[4:5], 0, v[28:29]
	v_mad_i64_i32 v[12:13], s[24:25], v12, s62, v[10:11]
	v_add_co_u32_e32 v6, vcc, s50, v4
	v_lshl_add_u64 v[12:13], v[12:13], 0, s[56:57]
	v_add_u32_e32 v14, s90, v47
	v_addc_co_u32_e32 v7, vcc, 0, v5, vcc
	v_lshl_add_u64 v[12:13], v[12:13], 0, v[28:29]
	v_mad_i64_i32 v[10:11], s[24:25], v14, s62, v[10:11]
	v_add_co_u32_e32 v12, vcc, s50, v12
	v_lshl_add_u64 v[10:11], v[10:11], 0, s[56:57]
	s_nop 0
	v_addc_co_u32_e32 v13, vcc, 0, v13, vcc
	v_lshl_add_u64 v[10:11], v[10:11], 0, v[28:29]
	v_add_co_u32_e32 v14, vcc, 0x1000, v10
	global_load_dwordx4 v[2:5], v[2:3], off offset:3168
	s_nop 0
	global_load_dwordx4 v[6:9], v[6:7], off offset:3168
	v_addc_co_u32_e32 v15, vcc, 0, v11, vcc
	global_load_dwordx4 v[10:13], v[12:13], off offset:3168
	s_nop 0
	global_load_dwordx4 v[14:17], v[14:15], off offset:3168
	s_lshl_b32 s87, s87, 6
	s_waitcnt vmcnt(0) lgkmcnt(0)
	s_barrier
	s_and_saveexec_b64 s[24:25], s[6:7]
	s_cbranch_execz .LBB0_1607
	s_mov_b64 s[88:89], 0
	v_mov_b32_e32 v29, v180
.LBB0_1604:
	v_ashrrev_i32_e32 v73, 4, v29
	v_add_u32_e32 v74, s90, v73
	v_mad_i64_i32 v[74:75], vcc, v74, s62, v[22:23]
	global_load_dword v74, v[74:75], off
	v_add_u32_e32 v75, 0x200, v29
	v_cmp_lt_i32_e32 vcc, s63, v29
	v_lshl_add_u32 v73, v73, 2, v59
	s_or_b64 s[88:89], vcc, s[88:89]
	v_mov_b32_e32 v29, v75
	s_waitcnt vmcnt(0) lgkmcnt(0)
	ds_write_b32 v73, v74
	s_andn2_b64 exec, exec, s[88:89]
	s_cbranch_execnz .LBB0_1604
	s_or_b64 exec, exec, s[88:89]
	s_mov_b64 s[88:89], 0
	v_mov_b32_e32 v29, v43
	v_mov_b32_e32 v73, v61
.LBB0_1606:
	v_mov_b64_e32 v[74:75], s[0:1]
	global_load_dwordx2 v[74:75], v[74:75], off offset:152 sc0 sc1
	s_waitcnt vmcnt(0)
	v_and_b32_e32 v76, 0xffffff00, v29
	v_ashrrev_i32_e32 v77, 31, v76
	s_lshl_b32 s56, s87, 2
	v_add_u32_e32 v73, 0x200, v73
	v_cmp_lt_i32_e32 vcc, s63, v73
	s_or_b64 s[88:89], vcc, s[88:89]
	s_waitcnt lgkmcnt(0)
	v_lshl_add_u64 v[74:75], v[76:77], 2, v[74:75]
	v_lshl_add_u64 v[74:75], v[74:75], 0, s[56:57]
	v_lshl_add_u64 v[74:75], v[74:75], 0, v[178:179]
	global_load_dword v74, v[74:75], off
	v_add_u32_e32 v75, s4, v29
	v_add_u32_e32 v29, 0x800, v29
	s_waitcnt vmcnt(0)
	ds_write_b32 v75, v74
	s_andn2_b64 exec, exec, s[88:89]
	s_cbranch_execnz .LBB0_1606

.LBB0_1609:
	v_mov_b64_e32 v[74:75], s[0:1]
	global_load_dwordx2 v[74:75], v[74:75], off offset:160 sc0 sc1
	s_waitcnt vmcnt(0)
	v_ashrrev_i32_e32 v73, 6, v29
	v_add_u32_e32 v76, s87, v73
	v_ashrrev_i32_e32 v77, 31, v76
	v_lshl_add_u32 v79, v73, 2, s4
	s_mov_b32 s24, 0xbfb8aa3b
	s_waitcnt lgkmcnt(0)
	v_lshl_add_u64 v[74:75], v[76:77], 2, v[74:75]
	global_load_dword v78, v[74:75], off
	ds_read2st64_b32 v[74:75], v60 offset1:1
	ds_read2st64_b32 v[76:77], v79 offset1:1
	s_waitcnt vmcnt(0) lgkmcnt(0)
	v_fmac_f32_e32 v78, v74, v76
	v_fmac_f32_e32 v78, v75, v77
	ds_read2st64_b32 v[74:75], v60 offset0:2 offset1:3
	ds_read2st64_b32 v[76:77], v79 offset0:2 offset1:3
	s_waitcnt lgkmcnt(0)
	v_fmac_f32_e32 v78, v74, v76
	v_fmac_f32_e32 v78, v75, v77
	ds_read2st64_b32 v[74:75], v60 offset0:4 offset1:5
	ds_read2st64_b32 v[76:77], v79 offset0:4 offset1:5
	s_waitcnt lgkmcnt(0)
	v_fmac_f32_e32 v78, v74, v76
	v_fmac_f32_e32 v78, v75, v77
	ds_read2st64_b32 v[74:75], v60 offset0:6 offset1:7
	ds_read2st64_b32 v[76:77], v79 offset0:6 offset1:7
	s_waitcnt lgkmcnt(0)
	v_pk_mul_f32 v[74:75], v[74:75], v[76:77]
	s_nop 0
	v_add_f32_e32 v74, v78, v74
	v_add_f32_e32 v78, v74, v75
	ds_read2st64_b32 v[74:75], v60 offset0:8 offset1:9
	ds_read2st64_b32 v[76:77], v79 offset0:8 offset1:9
	s_waitcnt lgkmcnt(0)
	v_pk_mul_f32 v[74:75], v[74:75], v[76:77]
	s_nop 0
	v_add_f32_e32 v74, v78, v74
	v_add_f32_e32 v78, v74, v75
	ds_read2st64_b32 v[74:75], v60 offset0:10 offset1:11
	ds_read2st64_b32 v[76:77], v79 offset0:10 offset1:11
	s_waitcnt lgkmcnt(0)
	v_pk_mul_f32 v[74:75], v[74:75], v[76:77]
	s_nop 0
	v_add_f32_e32 v74, v78, v74
	v_add_f32_e32 v78, v74, v75
	ds_read2st64_b32 v[74:75], v60 offset0:12 offset1:13
	ds_read2st64_b32 v[76:77], v79 offset0:12 offset1:13
	s_waitcnt lgkmcnt(0)
	v_pk_mul_f32 v[74:75], v[74:75], v[76:77]
	s_nop 0
	v_add_f32_e32 v74, v78, v74
	v_add_f32_e32 v78, v74, v75
	ds_read2st64_b32 v[74:75], v60 offset0:14 offset1:15
	ds_read2st64_b32 v[76:77], v79 offset0:14 offset1:15
	s_waitcnt lgkmcnt(0)
	v_pk_mul_f32 v[74:75], v[74:75], v[76:77]
	s_nop 0
	v_add_f32_e32 v74, v78, v74
	v_add_f32_e32 v74, v74, v75
	v_min_f32_e32 v75, 0, v74
	v_mul_f32_e64 v74, |v74|, s24
	v_exp_f32_e32 v74, v74
	s_mov_b32 s24, 0x800000
	v_add_f32_e32 v74, 1.0, v74
	v_cmp_gt_f32_e32 vcc, s24, v74
	s_mov_b32 s24, 0x3f317217
	s_nop 0
	v_cndmask_b32_e64 v76, 0, 32, vcc
	v_ldexp_f32 v74, v74, v76
	v_log_f32_e32 v74, v74
	s_nop 0
	v_mul_f32_e32 v76, 0x3f317217, v74
	v_fma_f32 v76, v74, s24, -v76
	v_fmac_f32_e32 v76, 0x3377d1cf, v74
	s_mov_b32 s24, 0x7f800000
	v_fmac_f32_e32 v76, 0x3f317217, v74
	v_cmp_lt_f32_e64 s[24:25], |v74|, s24
	s_nop 1
	v_cndmask_b32_e64 v74, v74, v76, s[24:25]
	v_cndmask_b32_e32 v76, 0, v183, vcc
	v_sub_f32_e32 v74, v74, v76
	v_sub_f32_e32 v74, v75, v74
	v_mul_f32_e32 v76, 0x3d800000, v74
	v_mad_u64_u32 v[74:75], s[24:25], v73, s51, v[18:19]
	s_movk_i32 s24, 0xdff
	v_add_u32_e32 v73, 0x200, v29
	v_cmp_lt_i32_e32 vcc, s24, v29
	s_or_b64 s[90:91], vcc, s[90:91]
	v_mov_b32_e32 v29, v73
	ds_write_b32 v74, v76
	s_andn2_b64 exec, exec, s[90:91]
	s_cbranch_execnz .LBB0_1609
.LBB0_1610:
	s_or_b64 exec, exec, s[88:89]
	v_add_u32_e32 v29, s83, v18
	s_waitcnt lgkmcnt(0)
	s_barrier
	ds_read2_b32 v[74:75], v29 offset1:65
	s_ashr_i32 s87, s86, 31
	s_lshl_b64 s[24:25], s[86:87], 14
	s_waitcnt lgkmcnt(0)
	ds_bpermute_b32 v73, v19, v74
	ds_bpermute_b32 v76, v19, v75
	s_waitcnt lgkmcnt(1)
	v_add_f32_e32 v73, v74, v73
	s_waitcnt lgkmcnt(0)
	v_add_f32_e32 v76, v75, v76
	v_cndmask_b32_e64 v73, v73, v74, s[10:11]
	v_cndmask_b32_e64 v74, v76, v75, s[10:11]
	ds_bpermute_b32 v75, v30, v73
	ds_bpermute_b32 v76, v30, v74
	s_waitcnt lgkmcnt(1)
	v_add_f32_e32 v75, v73, v75
	v_cndmask_b32_e64 v73, v75, v73, s[12:13]
	ds_bpermute_b32 v77, v31, v73
	s_waitcnt lgkmcnt(1)
	v_add_f32_e32 v76, v74, v76
	v_cndmask_b32_e64 v76, v76, v74, s[12:13]
	ds_bpermute_b32 v78, v31, v76
	ds_read2_b32 v[74:75], v29 offset0:130 offset1:195
	s_waitcnt lgkmcnt(2)
	v_add_f32_e32 v77, v73, v77
	v_cndmask_b32_e64 v73, v77, v73, s[14:15]
	ds_bpermute_b32 v77, v32, v73
	s_waitcnt lgkmcnt(2)
	v_add_f32_e32 v78, v76, v78
	v_cndmask_b32_e64 v76, v78, v76, s[14:15]
	ds_bpermute_b32 v78, v32, v76
	s_waitcnt lgkmcnt(2)
	ds_bpermute_b32 v79, v19, v74
	s_waitcnt lgkmcnt(2)
	v_add_f32_e32 v77, v73, v77
	v_cndmask_b32_e64 v73, v77, v73, s[16:17]
	ds_bpermute_b32 v77, v33, v73
	s_waitcnt lgkmcnt(2)
	v_add_f32_e32 v78, v76, v78
	v_cndmask_b32_e64 v76, v78, v76, s[16:17]
	s_waitcnt lgkmcnt(1)
	v_add_f32_e32 v79, v74, v79
	ds_bpermute_b32 v78, v33, v76
	v_cndmask_b32_e64 v74, v79, v74, s[10:11]
	ds_bpermute_b32 v79, v30, v74
	s_waitcnt lgkmcnt(2)
	v_add_f32_e32 v77, v73, v77
	v_cndmask_b32_e64 v73, v77, v73, s[18:19]
	ds_bpermute_b32 v77, v34, v73
	s_waitcnt lgkmcnt(2)
	v_add_f32_e32 v78, v76, v78
	v_cndmask_b32_e64 v76, v78, v76, s[18:19]
	s_waitcnt lgkmcnt(1)
	v_add_f32_e32 v79, v74, v79
	ds_bpermute_b32 v78, v34, v76
	v_cndmask_b32_e64 v74, v79, v74, s[12:13]
	ds_bpermute_b32 v79, v31, v74
	s_waitcnt lgkmcnt(2)
	v_add_f32_e32 v77, v73, v77
	v_cndmask_b32_e64 v73, v77, v73, s[20:21]
	ds_bpermute_b32 v77, v19, v75
	s_waitcnt lgkmcnt(2)
	v_add_f32_e32 v78, v76, v78
	v_cndmask_b32_e64 v76, v78, v76, s[20:21]
	s_waitcnt lgkmcnt(1)
	v_add_f32_e32 v78, v74, v79
	v_cndmask_b32_e64 v74, v78, v74, s[14:15]
	s_waitcnt lgkmcnt(0)
	v_add_f32_e32 v77, v75, v77
	ds_bpermute_b32 v78, v32, v74
	v_cndmask_b32_e64 v75, v77, v75, s[10:11]
	ds_bpermute_b32 v77, v30, v75
	ds_write2_b32 v29, v73, v76 offset1:65
	s_waitcnt lgkmcnt(2)
	v_add_f32_e32 v73, v74, v78
	v_cndmask_b32_e64 v73, v73, v74, s[16:17]
	s_waitcnt lgkmcnt(1)
	v_add_f32_e32 v74, v75, v77
	v_cndmask_b32_e64 v77, v74, v75, s[12:13]
	v_add_u32_e32 v78, 0x400, v29
	ds_read2_b32 v[74:75], v78 offset0:4 offset1:69
	ds_bpermute_b32 v79, v31, v77
	ds_bpermute_b32 v76, v33, v73
	s_waitcnt lgkmcnt(2)
	ds_bpermute_b32 v80, v19, v74
	s_waitcnt lgkmcnt(2)
	v_add_f32_e32 v79, v77, v79
	v_cndmask_b32_e64 v77, v79, v77, s[14:15]
	ds_bpermute_b32 v79, v32, v77
	s_waitcnt lgkmcnt(2)
	v_add_f32_e32 v76, v73, v76
	v_cndmask_b32_e64 v73, v76, v73, s[18:19]
	s_waitcnt lgkmcnt(1)
	v_add_f32_e32 v80, v74, v80
	ds_bpermute_b32 v76, v34, v73
	v_cndmask_b32_e64 v74, v80, v74, s[10:11]
	ds_bpermute_b32 v80, v30, v74
	s_waitcnt lgkmcnt(2)
	v_add_f32_e32 v79, v77, v79
	v_cndmask_b32_e64 v77, v79, v77, s[16:17]
	ds_bpermute_b32 v79, v33, v77
	s_waitcnt lgkmcnt(2)
	v_add_f32_e32 v76, v73, v76
	v_cndmask_b32_e64 v73, v76, v73, s[20:21]
	s_waitcnt lgkmcnt(1)
	v_add_f32_e32 v76, v74, v80
	v_cndmask_b32_e64 v74, v76, v74, s[12:13]
	ds_bpermute_b32 v76, v31, v74
	s_waitcnt lgkmcnt(1)
	v_add_f32_e32 v79, v77, v79
	v_cndmask_b32_e64 v77, v79, v77, s[18:19]
	ds_bpermute_b32 v79, v19, v75
	ds_bpermute_b32 v80, v34, v77
	s_waitcnt lgkmcnt(2)
	v_add_f32_e32 v76, v74, v76
	v_cndmask_b32_e64 v74, v76, v74, s[14:15]
	ds_bpermute_b32 v76, v32, v74
	s_waitcnt lgkmcnt(2)
	v_add_f32_e32 v79, v75, v79
	v_cndmask_b32_e64 v75, v79, v75, s[10:11]
	ds_bpermute_b32 v79, v30, v75
	s_waitcnt lgkmcnt(2)
	v_add_f32_e32 v80, v77, v80
	s_waitcnt lgkmcnt(1)
	v_add_f32_e32 v76, v74, v76
	v_cndmask_b32_e64 v74, v76, v74, s[16:17]
	ds_bpermute_b32 v76, v33, v74
	s_waitcnt lgkmcnt(1)
	v_add_f32_e32 v79, v75, v79
	v_cndmask_b32_e64 v75, v79, v75, s[12:13]
	ds_bpermute_b32 v79, v31, v75
	v_cndmask_b32_e64 v77, v80, v77, s[20:21]
	s_waitcnt lgkmcnt(1)
	v_add_f32_e32 v76, v74, v76
	v_cndmask_b32_e64 v76, v76, v74, s[18:19]
	ds_write2_b32 v29, v73, v77 offset0:130 offset1:195
	s_waitcnt lgkmcnt(1)
	v_add_f32_e32 v74, v75, v79
	v_cndmask_b32_e64 v79, v74, v75, s[14:15]
	ds_read2_b32 v[74:75], v78 offset0:134 offset1:199
	ds_bpermute_b32 v80, v34, v76
	ds_bpermute_b32 v81, v32, v79
	s_waitcnt lgkmcnt(2)
	ds_bpermute_b32 v73, v19, v74
	ds_bpermute_b32 v77, v19, v75
	s_waitcnt lgkmcnt(3)
	v_add_f32_e32 v29, v76, v80
	v_cndmask_b32_e64 v29, v29, v76, s[20:21]
	s_waitcnt lgkmcnt(2)
	v_add_f32_e32 v76, v79, v81
	s_waitcnt lgkmcnt(1)
	v_add_f32_e32 v73, v74, v73
	v_cndmask_b32_e64 v73, v73, v74, s[10:11]
	s_waitcnt lgkmcnt(0)
	v_add_f32_e32 v77, v75, v77
	ds_bpermute_b32 v74, v30, v73
	v_cndmask_b32_e64 v75, v77, v75, s[10:11]
	ds_bpermute_b32 v77, v30, v75
	v_cndmask_b32_e64 v76, v76, v79, s[16:17]
	ds_bpermute_b32 v79, v33, v76
	s_waitcnt lgkmcnt(2)
	v_add_f32_e32 v74, v73, v74
	v_cndmask_b32_e64 v73, v74, v73, s[12:13]
	s_waitcnt lgkmcnt(1)
	v_add_f32_e32 v77, v75, v77
	ds_bpermute_b32 v74, v31, v73
	v_cndmask_b32_e64 v75, v77, v75, s[12:13]
	ds_bpermute_b32 v77, v31, v75
	s_waitcnt lgkmcnt(2)
	v_add_f32_e32 v79, v76, v79
	v_cndmask_b32_e64 v76, v79, v76, s[18:19]
	s_waitcnt lgkmcnt(1)
	v_add_f32_e32 v74, v73, v74
	v_cndmask_b32_e64 v73, v74, v73, s[14:15]
	s_waitcnt lgkmcnt(0)
	v_add_f32_e32 v77, v75, v77
	ds_bpermute_b32 v74, v32, v73
	v_cndmask_b32_e64 v75, v77, v75, s[14:15]
	ds_bpermute_b32 v77, v32, v75
	ds_bpermute_b32 v79, v34, v76
	s_waitcnt lgkmcnt(2)
	v_add_f32_e32 v74, v73, v74
	v_cndmask_b32_e64 v73, v74, v73, s[16:17]
	s_waitcnt lgkmcnt(1)
	v_add_f32_e32 v77, v75, v77
	ds_bpermute_b32 v74, v33, v73
	v_cndmask_b32_e64 v75, v77, v75, s[16:17]
	ds_bpermute_b32 v77, v33, v75
	s_waitcnt lgkmcnt(2)
	v_add_f32_e32 v79, v76, v79
	v_cndmask_b32_e64 v76, v79, v76, s[20:21]
	s_waitcnt lgkmcnt(1)
	v_add_f32_e32 v74, v73, v74
	v_cndmask_b32_e64 v73, v74, v73, s[18:19]
	s_waitcnt lgkmcnt(0)
	v_add_f32_e32 v77, v75, v77
	ds_bpermute_b32 v74, v34, v73
	v_cndmask_b32_e64 v75, v77, v75, s[18:19]
	ds_bpermute_b32 v77, v34, v75
	ds_write2_b32 v78, v29, v76 offset0:4 offset1:69
	s_waitcnt lgkmcnt(2)
	v_add_f32_e32 v29, v73, v74
	v_cndmask_b32_e64 v29, v29, v73, s[20:21]
	s_waitcnt lgkmcnt(1)
	v_add_f32_e32 v73, v75, v77
	v_cndmask_b32_e64 v73, v73, v75, s[20:21]
	ds_write2_b32 v78, v29, v73 offset0:134 offset1:199
	s_waitcnt lgkmcnt(0)
	s_barrier
	ds_read_b32 v29, v49
	ds_read_b32 v73, v48 offset:252
	s_waitcnt lgkmcnt(0)
	v_sub_f32_e32 v73, v73, v29
	v_mul_f32_e32 v73, 0x3fb8aa3b, v73
	v_exp_f32_e32 v73, v73
	s_nop 0
	v_mul_f32_e32 v72, v72, v73
	ds_write_b32 v50, v72 offset:16640
	v_lshl_add_u64 v[72:73], v[26:27], 0, s[24:25]
	global_store_dword v[72:73], v29, off
	ds_read_b32 v29, v51
	ds_read_b32 v74, v48 offset:252
	s_movk_i32 s24, 0x2000
	s_waitcnt lgkmcnt(0)
	v_sub_f32_e32 v74, v74, v29
	v_mul_f32_e32 v74, 0x3fb8aa3b, v74
	v_exp_f32_e32 v74, v74
	s_nop 0
	v_mul_f32_e32 v71, v71, v74
	ds_write_b32 v50, v71 offset:18688
	global_store_dword v[72:73], v29, off offset:2048
	ds_read_b32 v29, v52
	ds_read_b32 v71, v48 offset:252
	s_waitcnt lgkmcnt(0)
	v_sub_f32_e32 v71, v71, v29
	v_mul_f32_e32 v71, 0x3fb8aa3b, v71
	v_exp_f32_e32 v71, v71
	s_nop 0
	v_mul_f32_e32 v70, v70, v71
	ds_write_b32 v50, v70 offset:20736
	v_add_co_u32_e32 v70, vcc, s50, v72
	s_nop 1
	v_addc_co_u32_e32 v71, vcc, 0, v73, vcc
	global_store_dword v[70:71], v29, off
	ds_read_b32 v29, v53
	ds_read_b32 v74, v48 offset:252
	s_waitcnt lgkmcnt(0)
	v_sub_f32_e32 v74, v74, v29
	v_mul_f32_e32 v74, 0x3fb8aa3b, v74
	v_exp_f32_e32 v74, v74
	s_nop 0
	v_mul_f32_e32 v69, v69, v74
	ds_write_b32 v50, v69 offset:22784
	global_store_dword v[70:71], v29, off offset:2048
	ds_read_b32 v29, v54
	ds_read_b32 v69, v48 offset:252
	s_waitcnt lgkmcnt(0)
	v_sub_f32_e32 v69, v69, v29
	v_mul_f32_e32 v69, 0x3fb8aa3b, v69
	v_exp_f32_e32 v69, v69
	s_nop 0
	v_mul_f32_e32 v68, v68, v69
	ds_write_b32 v50, v68 offset:24832
	v_add_co_u32_e32 v68, vcc, s24, v72
	s_mov_b32 s24, 0
	s_nop 0
	v_addc_co_u32_e32 v69, vcc, 0, v73, vcc
	global_store_dword v[68:69], v29, off
	ds_read_b32 v29, v55
	ds_read_b32 v70, v48 offset:252
	s_waitcnt lgkmcnt(0)
	v_sub_f32_e32 v70, v70, v29
	v_mul_f32_e32 v70, 0x3fb8aa3b, v70
	v_exp_f32_e32 v70, v70
	s_nop 0
	v_mul_f32_e32 v67, v67, v70
	ds_write_b32 v50, v67 offset:26880
	global_store_dword v[68:69], v29, off offset:2048
	ds_read_b32 v29, v56
	ds_read_b32 v67, v48 offset:252
	s_waitcnt lgkmcnt(0)
	v_sub_f32_e32 v67, v67, v29
	v_mul_f32_e32 v67, 0x3fb8aa3b, v67
	v_exp_f32_e32 v67, v67
	s_nop 0
	v_mul_f32_e32 v66, v66, v67
	ds_write_b32 v50, v66 offset:28928
	v_add_co_u32_e32 v66, vcc, s62, v72
	s_nop 1
	v_addc_co_u32_e32 v67, vcc, 0, v73, vcc
	global_store_dword v[66:67], v29, off
	ds_read_b32 v29, v57
	ds_read_b32 v68, v48 offset:252
	s_waitcnt lgkmcnt(0)
	v_sub_f32_e32 v68, v68, v29
	v_mul_f32_e32 v68, 0x3fb8aa3b, v68
	v_exp_f32_e32 v68, v68
	s_nop 0
	v_mul_f32_e32 v65, v65, v68
	ds_write_b32 v50, v65 offset:30976
	global_store_dword v[66:67], v29, off offset:2048
	ds_write_b128 v58, v[2:5] offset:33024
	ds_write_b128 v58, v[6:9] offset:41216
	ds_write_b128 v58, v[10:13] offset:49408
	ds_write_b128 v58, v[14:17] offset:57600
	v_mov_b32_e32 v2, 0
	v_mov_b32_e32 v29, v62
	v_mov_b32_e32 v3, v2
	v_mov_b32_e32 v4, v2
	v_mov_b32_e32 v5, v2
	v_mov_b32_e32 v6, v2
	v_mov_b32_e32 v7, v2
	v_mov_b32_e32 v8, v2
	v_mov_b32_e32 v9, v2
	v_mov_b32_e32 v10, v2
	v_mov_b32_e32 v11, v2
	v_mov_b32_e32 v12, v2
	v_mov_b32_e32 v13, v2
	v_mov_b32_e32 v14, v2
	v_mov_b32_e32 v15, v2
	v_mov_b32_e32 v16, v2
	v_mov_b32_e32 v17, v2
	s_waitcnt lgkmcnt(0)
	s_barrier
.LBB0_1611:
	v_add_u32_e32 v65, s24, v63
	ds_read2st64_b32 v[66:67], v65 offset1:2
	ds_read2st64_b32 v[68:69], v29 offset1:4
	s_addk_i32 s24, 0x1000
	s_cmpk_eq_i32 s24, 0x4000
	s_waitcnt lgkmcnt(0)
	v_mfma_f32_32x32x2_f32 v[2:17], v66, v68, v[2:17]
	v_mfma_f32_32x32x2_f32 v[2:17], v67, v69, v[2:17]
	ds_read2st64_b32 v[66:67], v65 offset0:4 offset1:6
	ds_read2st64_b32 v[68:69], v29 offset0:8 offset1:12
	s_waitcnt lgkmcnt(0)
	v_mfma_f32_32x32x2_f32 v[2:17], v66, v68, v[2:17]
	v_mfma_f32_32x32x2_f32 v[2:17], v67, v69, v[2:17]
	ds_read2st64_b32 v[66:67], v65 offset0:8 offset1:10
	ds_read2st64_b32 v[68:69], v29 offset0:16 offset1:20
	s_waitcnt lgkmcnt(0)
	v_mfma_f32_32x32x2_f32 v[2:17], v66, v68, v[2:17]
	v_mfma_f32_32x32x2_f32 v[2:17], v67, v69, v[2:17]
	ds_read2st64_b32 v[66:67], v65 offset0:12 offset1:14
	ds_read2st64_b32 v[68:69], v29 offset0:24 offset1:28
	v_add_u32_e32 v29, 0x2000, v29
	s_waitcnt lgkmcnt(0)
	v_mfma_f32_32x32x2_f32 v[2:17], v66, v68, v[2:17]
	v_mfma_f32_32x32x2_f32 v[2:17], v67, v69, v[2:17]
	s_cbranch_scc0 .LBB0_1611
	s_lshl_b64 s[24:25], s[86:87], 6
	s_add_u32 s88, s24, s5
	s_addc_u32 s89, s25, s44
	s_lshl_b64 s[88:89], s[88:89], 9
	v_lshl_add_u64 v[66:67], v[24:25], 0, s[88:89]
	s_nop 11
	global_store_dword v[66:67], v2, off
	global_store_dword v[66:67], v3, off offset:512
	global_store_dword v[66:67], v4, off offset:1024
	global_store_dword v[66:67], v5, off offset:1536
	v_add_co_u32_e32 v2, vcc, 0x1000, v66
	s_nop 1
	v_addc_co_u32_e32 v3, vcc, 0, v67, vcc
	global_store_dword v[2:3], v6, off
	global_store_dword v[2:3], v7, off offset:512
	global_store_dword v[2:3], v8, off offset:1024
	global_store_dword v[2:3], v9, off offset:1536
	v_add_co_u32_e32 v2, vcc, 0x2000, v66
	s_nop 1
	v_addc_co_u32_e32 v3, vcc, 0, v67, vcc
	global_store_dword v[2:3], v10, off
	global_store_dword v[2:3], v11, off offset:512
	global_store_dword v[2:3], v12, off offset:1024
	global_store_dword v[2:3], v13, off offset:1536
	v_add_co_u32_e32 v2, vcc, 0x3000, v66
	s_nop 1
	v_addc_co_u32_e32 v3, vcc, 0, v67, vcc
	global_store_dword v[2:3], v14, off
	global_store_dword v[2:3], v15, off offset:512
	global_store_dword v[2:3], v16, off offset:1024
	global_store_dword v[2:3], v17, off offset:1536
	s_and_saveexec_b64 s[88:89], s[22:23]
	s_cbranch_execz .LBB0_1601
	ds_read_b32 v4, v64 offset:252
	v_lshl_add_u64 v[2:3], s[24:25], 2, v[20:21]
	s_waitcnt lgkmcnt(0)
	v_mul_f32_e32 v4, 0x3fb8aa3b, v4
	v_exp_f32_e32 v4, v4
	global_store_dword v[2:3], v4, off
	s_branch .LBB0_1601

.LBB0_1622:
	s_load_dwordx4 s[92:95], s[0:1], 0xd0
	v_mov_b32_e32 v18, v0
	s_add_i32 s2, s40, 0xffffff70
	v_readlane_b32 s50, v228, 15
	s_cmp_lt_u32 s2, 64
	v_readfirstlane_b32 s2, v18
	v_readlane_b32 s97, v228, 14
	v_readlane_b32 s51, v228, 16
	s_cbranch_scc0 .LBB0_1636
	s_lshl_b32 s3, s40, 4
	s_and_b32 s12, s3, 0xf00
	s_and_b32 s5, s40, 15
	s_addk_i32 s12, 0xf700
	s_lshl_b32 s6, s12, 4
	s_lshl_b32 s7, s5, 6
	s_or_b32 s6, s7, s6
	s_lshr_b32 s3, s12, 7
	s_and_b32 s10, s6, 0x7fffe3c0
	v_ashrrev_i32_e32 v19, 6, v18
	s_and_b32 s3, s3, 2
	s_waitcnt lgkmcnt(0)
	v_add_u32_e32 v2, s10, v19
	s_movk_i32 s11, 0x3000
	v_mov_b64_e32 v[10:11], s[46:47]
	v_add_u32_e32 v24, 0x200, v18
	v_and_b32_e32 v26, 63, v18
	s_mov_b32 s7, 0
	v_mad_i64_i32 v[2:3], s[8:9], v2, s11, v[10:11]
	s_lshl_b32 s6, s3, 8
	v_ashrrev_i32_e32 v29, 6, v24
	v_mov_b32_e32 v23, 0
	v_lshl_add_u64 v[2:3], v[2:3], 0, s[6:7]
	v_lshlrev_b32_e32 v22, 2, v26
	v_add_u32_e32 v4, s10, v29
	v_add_u32_e32 v25, 0x400, v18
	v_lshl_add_u64 v[2:3], v[2:3], 0, v[22:23]
	s_movk_i32 s13, 0x1000
	v_mad_i64_i32 v[4:5], s[8:9], v4, s11, v[10:11]
	v_ashrrev_i32_e32 v33, 6, v25
	v_add_co_u32_e32 v2, vcc, s13, v2
	v_lshl_add_u64 v[4:5], v[4:5], 0, s[6:7]
	v_add_u32_e32 v6, s10, v33
	v_add_u32_e32 v43, 0x600, v18
	v_addc_co_u32_e32 v3, vcc, 0, v3, vcc
	v_lshl_add_u64 v[4:5], v[4:5], 0, v[22:23]
	v_mad_i64_i32 v[6:7], s[8:9], v6, s11, v[10:11]
	v_ashrrev_i32_e32 v30, 6, v43
	v_add_co_u32_e32 v4, vcc, s13, v4
	v_lshl_add_u64 v[6:7], v[6:7], 0, s[6:7]
	v_add_u32_e32 v8, s10, v30
	v_add_u32_e32 v12, 0x800, v18
	v_addc_co_u32_e32 v5, vcc, 0, v5, vcc
	v_lshl_add_u64 v[6:7], v[6:7], 0, v[22:23]
	v_mad_i64_i32 v[8:9], s[8:9], v8, s11, v[10:11]
	v_ashrrev_i32_e32 v32, 6, v12
	v_add_co_u32_e32 v6, vcc, s13, v6
	v_lshl_add_u64 v[8:9], v[8:9], 0, s[6:7]
	v_add_u32_e32 v12, s10, v32
	v_add_u32_e32 v14, 0xa00, v18
	v_addc_co_u32_e32 v7, vcc, 0, v7, vcc
	v_lshl_add_u64 v[8:9], v[8:9], 0, v[22:23]
	v_mad_i64_i32 v[12:13], s[8:9], v12, s11, v[10:11]
	v_ashrrev_i32_e32 v28, 6, v14
	v_add_co_u32_e32 v8, vcc, s13, v8
	v_lshl_add_u64 v[12:13], v[12:13], 0, s[6:7]
	v_add_u32_e32 v14, s10, v28
	v_add_u32_e32 v16, 0xc00, v18
	v_addc_co_u32_e32 v9, vcc, 0, v9, vcc
	v_lshl_add_u64 v[12:13], v[12:13], 0, v[22:23]
	v_mad_i64_i32 v[14:15], s[8:9], v14, s11, v[10:11]
	v_ashrrev_i32_e32 v31, 6, v16
	v_add_co_u32_e32 v12, vcc, s13, v12
	v_lshl_add_u64 v[14:15], v[14:15], 0, s[6:7]
	v_add_u32_e32 v16, s10, v31
	v_add_u32_e32 v20, 0xe00, v18
	v_addc_co_u32_e32 v13, vcc, 0, v13, vcc
	v_lshl_add_u64 v[14:15], v[14:15], 0, v[22:23]
	v_mad_i64_i32 v[16:17], s[8:9], v16, s11, v[10:11]
	v_ashrrev_i32_e32 v27, 6, v20
	v_add_co_u32_e32 v14, vcc, s13, v14
	v_lshl_add_u64 v[16:17], v[16:17], 0, s[6:7]
	v_add_u32_e32 v20, s10, v27
	v_addc_co_u32_e32 v15, vcc, 0, v15, vcc
	v_lshl_add_u64 v[16:17], v[16:17], 0, v[22:23]
	v_mad_i64_i32 v[20:21], s[8:9], v20, s11, v[10:11]
	v_add_co_u32_e32 v16, vcc, s13, v16
	v_lshl_add_u64 v[20:21], v[20:21], 0, s[6:7]
	s_nop 0
	v_addc_co_u32_e32 v17, vcc, 0, v17, vcc
	v_lshl_add_u64 v[20:21], v[20:21], 0, v[22:23]
	v_add_co_u32_e32 v20, vcc, s13, v20
	v_lshlrev_b32_e32 v35, 2, v18
	s_nop 0
	v_addc_co_u32_e32 v21, vcc, 0, v21, vcc
	global_load_dword v42, v[2:3], off offset:2144
	global_load_dword v41, v[4:5], off offset:2144
	global_load_dword v40, v[6:7], off offset:2144
	global_load_dword v39, v[8:9], off offset:2144
	global_load_dword v38, v[12:13], off offset:2144
	global_load_dword v37, v[14:15], off offset:2144
	global_load_dword v36, v[16:17], off offset:2144
	global_load_dword v34, v[20:21], off offset:2144
	v_ashrrev_i32_e32 v2, 5, v18
	v_and_b32_e32 v4, 0x7c, v35
	v_add_u32_e32 v2, s10, v2
	v_mad_i64_i32 v[2:3], s[8:9], v2, s11, v[10:11]
	s_lshl_b32 s6, s3, 9
	v_lshlrev_b32_e32 v20, 2, v4
	v_ashrrev_i32_e32 v4, 5, v24
	v_lshl_add_u64 v[2:3], v[2:3], 0, s[6:7]
	v_mov_b32_e32 v21, v23
	v_add_u32_e32 v4, s10, v4
	v_lshl_add_u64 v[2:3], v[2:3], 0, v[20:21]
	v_mad_i64_i32 v[4:5], s[8:9], v4, s11, v[10:11]
	v_ashrrev_i32_e32 v12, 5, v25
	v_add_co_u32_e32 v2, vcc, s13, v2
	v_lshl_add_u64 v[4:5], v[4:5], 0, s[6:7]
	v_add_u32_e32 v12, s10, v12
	v_addc_co_u32_e32 v3, vcc, 0, v3, vcc
	v_lshl_add_u64 v[4:5], v[4:5], 0, v[20:21]
	v_mad_i64_i32 v[12:13], s[8:9], v12, s11, v[10:11]
	v_ashrrev_i32_e32 v14, 5, v43
	v_add_co_u32_e32 v6, vcc, s13, v4
	v_lshl_add_u64 v[12:13], v[12:13], 0, s[6:7]
	v_add_u32_e32 v14, s10, v14
	v_addc_co_u32_e32 v7, vcc, 0, v5, vcc
	v_lshl_add_u64 v[12:13], v[12:13], 0, v[20:21]
	v_mad_i64_i32 v[10:11], s[8:9], v14, s11, v[10:11]
	v_add_co_u32_e32 v12, vcc, s13, v12
	v_lshl_add_u64 v[10:11], v[10:11], 0, s[6:7]
	s_nop 0
	v_addc_co_u32_e32 v13, vcc, 0, v13, vcc
	v_lshl_add_u64 v[10:11], v[10:11], 0, v[20:21]
	v_add_co_u32_e32 v14, vcc, 0x1000, v10
	global_load_dwordx4 v[2:5], v[2:3], off offset:3168
	s_nop 0
	global_load_dwordx4 v[6:9], v[6:7], off offset:3168
	v_addc_co_u32_e32 v15, vcc, 0, v11, vcc
	global_load_dwordx4 v[10:13], v[12:13], off offset:3168
	s_nop 0
	global_load_dwordx4 v[14:17], v[14:15], off offset:3168
	s_movk_i32 s6, 0x400
	s_lshl_b32 s3, s3, 6
	v_cmp_gt_i32_e32 vcc, s6, v18
	s_waitcnt vmcnt(0) lgkmcnt(0)
	s_barrier
	s_and_saveexec_b64 s[6:7], vcc
	s_cbranch_execz .LBB0_1628
	v_and_b32_e32 v21, 15, v18
	v_readlane_b32 s8, v228, 27
	v_lshlrev_b32_e32 v24, 2, v21
	v_mov_b32_e32 v25, v23
	v_readlane_b32 s9, v228, 28
	s_movk_i32 s13, 0x1ff
	v_mov_b32_e32 v23, v18
	v_lshl_add_u64 v[24:25], s[8:9], 0, v[24:25]
	v_readlane_b32 s8, v228, 19
	s_nop 1
	v_lshl_add_u32 v21, v21, 8, s8
	s_mov_b64 s[8:9], 0
.LBB0_1625:
	v_ashrrev_i32_e32 v43, 4, v23
	v_add_u32_e32 v44, s10, v43
	v_mad_i64_i32 v[44:45], s[14:15], v44, s11, v[24:25]
	global_load_dword v44, v[44:45], off
	v_add_u32_e32 v45, 0x200, v23
	v_cmp_lt_i32_e32 vcc, s13, v23
	v_lshl_add_u32 v43, v43, 2, v21
	s_or_b64 s[8:9], vcc, s[8:9]
	v_mov_b32_e32 v23, v45
	s_waitcnt vmcnt(0) lgkmcnt(0)
	ds_write_b32 v43, v44
	s_andn2_b64 exec, exec, s[8:9]
	s_cbranch_execnz .LBB0_1625
	s_or_b64 exec, exec, s[8:9]
	v_add_u32_e32 v21, 0xfffffe00, v18
	s_mov_b64 s[8:9], 0
	v_mov_b64_e32 v[24:25], s[0:1]
	s_lshl_b32 s10, s3, 2
	s_mov_b32 s11, 0
	v_mov_b32_e32 v23, 0
	s_movk_i32 s13, 0x1ff
	v_mov_b32_e32 v43, v35
.LBB0_1627:
	global_load_dwordx2 v[44:45], v[24:25], off offset:152 sc0 sc1
	s_waitcnt vmcnt(0)
	v_and_b32_e32 v46, 0xffffff00, v43
	v_ashrrev_i32_e32 v47, 31, v46
	v_add_u32_e32 v21, 0x200, v21
	v_cmp_lt_i32_e32 vcc, s13, v21
	s_or_b64 s[8:9], vcc, s[8:9]
	s_waitcnt lgkmcnt(0)
	v_lshl_add_u64 v[44:45], v[46:47], 2, v[44:45]
	v_lshl_add_u64 v[44:45], v[44:45], 0, s[10:11]
	v_lshl_add_u64 v[44:45], v[44:45], 0, v[22:23]
	global_load_dword v44, v[44:45], off
	v_add_u32_e32 v45, s4, v43
	v_add_u32_e32 v43, 0x800, v43
	s_waitcnt vmcnt(0)
	ds_write_b32 v45, v44
	s_andn2_b64 exec, exec, s[8:9]
	s_cbranch_execnz .LBB0_1627

.LBB0_1630:
	global_load_dwordx2 v[44:45], v[24:25], off offset:160 sc0 sc1
	s_waitcnt vmcnt(0)
	v_ashrrev_i32_e32 v60, 6, v43
	v_add_u32_e32 v46, s3, v60
	v_ashrrev_i32_e32 v47, 31, v46
	v_add_u32_e32 v79, 0x200, v43
	v_cmp_lt_i32_e32 vcc, s14, v43
	v_lshl_add_u32 v43, v60, 2, s4
	s_or_b64 s[8:9], vcc, s[8:9]
	v_mad_u64_u32 v[60:61], s[18:19], v60, s13, v[22:23]
	s_waitcnt lgkmcnt(0)
	v_lshl_add_u64 v[44:45], v[46:47], 2, v[44:45]
	global_load_dword v78, v[44:45], off
	ds_read2st64_b32 v[44:45], v21 offset1:1
	ds_read2st64_b32 v[46:47], v21 offset0:2 offset1:3
	ds_read2st64_b32 v[48:49], v21 offset0:4 offset1:5
	ds_read2st64_b32 v[50:51], v21 offset0:6 offset1:7
	ds_read2st64_b32 v[52:53], v21 offset0:8 offset1:9
	ds_read2st64_b32 v[54:55], v21 offset0:10 offset1:11
	ds_read2st64_b32 v[56:57], v21 offset0:12 offset1:13
	ds_read2st64_b32 v[58:59], v21 offset0:14 offset1:15
	ds_read2st64_b32 v[62:63], v43 offset1:1
	ds_read2st64_b32 v[64:65], v43 offset0:2 offset1:3
	ds_read2st64_b32 v[66:67], v43 offset0:4 offset1:5
	ds_read2st64_b32 v[68:69], v43 offset0:6 offset1:7
	ds_read2st64_b32 v[70:71], v43 offset0:8 offset1:9
	ds_read2st64_b32 v[72:73], v43 offset0:10 offset1:11
	ds_read2st64_b32 v[74:75], v43 offset0:12 offset1:13
	ds_read2st64_b32 v[76:77], v43 offset0:14 offset1:15
	s_waitcnt lgkmcnt(4)
	v_pk_mul_f32 v[50:51], v[50:51], v[68:69]
	s_waitcnt lgkmcnt(3)
	v_pk_mul_f32 v[52:53], v[52:53], v[70:71]
	s_waitcnt lgkmcnt(2)
	v_pk_mul_f32 v[54:55], v[54:55], v[72:73]
	s_waitcnt lgkmcnt(1)
	v_pk_mul_f32 v[56:57], v[56:57], v[74:75]
	s_waitcnt lgkmcnt(0)
	v_pk_mul_f32 v[58:59], v[58:59], v[76:77]
	s_waitcnt vmcnt(0)
	v_fmac_f32_e32 v78, v44, v62
	v_fmac_f32_e32 v78, v45, v63
	v_fmac_f32_e32 v78, v46, v64
	v_fmac_f32_e32 v78, v47, v65
	v_fmac_f32_e32 v78, v48, v66
	v_fmac_f32_e32 v78, v49, v67
	v_add_f32_e32 v43, v78, v50
	v_add_f32_e32 v43, v43, v51
	v_add_f32_e32 v43, v43, v52
	v_add_f32_e32 v43, v43, v53
	v_add_f32_e32 v43, v43, v54
	v_add_f32_e32 v43, v43, v55
	v_add_f32_e32 v43, v43, v56
	v_add_f32_e32 v43, v43, v57
	v_add_f32_e32 v43, v43, v58
	v_add_f32_e32 v44, v43, v59
	v_mul_f32_e64 v43, |v44|, s5
	v_exp_f32_e32 v45, v43
	v_min_f32_e32 v44, 0, v44
	v_mov_b32_e32 v43, v79
	v_add_f32_e32 v45, 1.0, v45
	v_cmp_gt_f32_e32 vcc, s10, v45
	s_nop 1
	v_cndmask_b32_e64 v46, 0, 32, vcc
	v_ldexp_f32 v45, v45, v46
	v_log_f32_e32 v45, v45
	v_cndmask_b32_e32 v46, 0, v23, vcc
	v_mul_f32_e32 v47, 0x3f317217, v45
	v_fma_f32 v47, v45, s11, -v47
	v_fmac_f32_e32 v47, 0x3377d1cf, v45
	v_fmac_f32_e32 v47, 0x3f317217, v45
	v_cmp_lt_f32_e64 vcc, |v45|, s12
	s_nop 1
	v_cndmask_b32_e32 v45, v45, v47, vcc
	v_sub_f32_e32 v45, v45, v46
	v_sub_f32_e32 v44, v44, v45
	v_mul_f32_e32 v44, 0x3d800000, v44
	ds_write_b32 v60, v44
	s_andn2_b64 exec, exec, s[8:9]
	s_cbranch_execnz .LBB0_1630
.LBB0_1631:
	s_or_b64 exec, exec, s[6:7]
	s_ashr_i32 s3, s2, 6
	s_mul_i32 s4, s3, 0x820
	s_add_i32 s4, s4, s96
	v_lshl_add_u32 v24, v26, 2, s4
	s_waitcnt lgkmcnt(0)
	s_barrier
	ds_read2_b32 v[22:23], v24 offset1:65
	v_and_b32_e32 v21, 64, v1
	v_add_u32_e32 v25, -1, v1
	v_cmp_lt_i32_e32 vcc, v25, v21
	v_subrev_u32_e32 v49, 32, v1
	v_cmp_lt_i32_e64 s[14:15], v49, v21
	v_cndmask_b32_e32 v25, v25, v1, vcc
	v_lshlrev_b32_e32 v25, 2, v25
	s_waitcnt lgkmcnt(0)
	ds_bpermute_b32 v43, v25, v22
	v_cmp_eq_u32_e32 vcc, 0, v26
	ds_bpermute_b32 v47, v25, v23
	s_movk_i32 s4, 0x104
	s_mov_b32 s17, 0
	s_waitcnt lgkmcnt(1)
	v_add_f32_e32 v43, v22, v43
	v_cndmask_b32_e32 v22, v43, v22, vcc
	v_add_u32_e32 v43, -2, v1
	v_cmp_lt_i32_e64 s[6:7], v43, v21
	s_waitcnt lgkmcnt(0)
	v_add_f32_e32 v47, v23, v47
	v_cndmask_b32_e32 v23, v47, v23, vcc
	v_cndmask_b32_e64 v43, v43, v1, s[6:7]
	v_lshlrev_b32_e32 v43, 2, v43
	ds_bpermute_b32 v44, v43, v22
	v_cmp_gt_u32_e64 s[6:7], 2, v26
	ds_bpermute_b32 v47, v43, v23
	s_and_b32 s3, s3, 3
	s_ashr_i32 s2, s2, 8
	s_waitcnt lgkmcnt(1)
	v_add_f32_e32 v44, v22, v44
	v_cndmask_b32_e64 v22, v44, v22, s[6:7]
	v_add_u32_e32 v44, -4, v1
	v_cmp_lt_i32_e64 s[8:9], v44, v21
	s_waitcnt lgkmcnt(0)
	v_add_f32_e32 v47, v23, v47
	v_cndmask_b32_e64 v23, v47, v23, s[6:7]
	v_cndmask_b32_e64 v44, v44, v1, s[8:9]
	v_lshlrev_b32_e32 v44, 2, v44
	ds_bpermute_b32 v45, v44, v22
	v_cmp_gt_u32_e64 s[8:9], 4, v26
	ds_bpermute_b32 v47, v44, v23
	s_waitcnt lgkmcnt(1)
	v_add_f32_e32 v45, v22, v45
	v_cndmask_b32_e64 v22, v45, v22, s[8:9]
	v_add_u32_e32 v45, -8, v1
	v_cmp_lt_i32_e64 s[10:11], v45, v21
	s_nop 1
	v_cndmask_b32_e64 v45, v45, v1, s[10:11]
	v_lshlrev_b32_e32 v45, 2, v45
	ds_bpermute_b32 v46, v45, v22
	v_cmp_gt_u32_e64 s[10:11], 8, v26
	s_waitcnt lgkmcnt(0)
	v_add_f32_e32 v46, v22, v46
	v_cndmask_b32_e64 v22, v46, v22, s[10:11]
	v_add_u32_e32 v46, -16, v1
	v_cmp_lt_i32_e64 s[12:13], v46, v21
	v_cndmask_b32_e64 v21, v49, v1, s[14:15]
	v_lshlrev_b32_e32 v21, 2, v21
	v_cndmask_b32_e64 v46, v46, v1, s[12:13]
	v_lshlrev_b32_e32 v46, 2, v46
	ds_bpermute_b32 v48, v46, v22
	v_cmp_gt_u32_e64 s[12:13], 16, v26
	v_cmp_gt_u32_e64 s[14:15], 32, v26
	s_waitcnt lgkmcnt(0)
	v_add_f32_e32 v48, v22, v48
	v_cndmask_b32_e64 v48, v48, v22, s[12:13]
	v_add_f32_e32 v22, v23, v47
	v_cndmask_b32_e64 v47, v22, v23, s[8:9]
	ds_read2_b32 v[22:23], v24 offset0:130 offset1:195
	ds_bpermute_b32 v50, v45, v47
	ds_bpermute_b32 v51, v21, v48
	s_waitcnt lgkmcnt(2)
	ds_bpermute_b32 v49, v25, v22
	s_waitcnt lgkmcnt(2)
	v_add_f32_e32 v50, v47, v50
	v_cndmask_b32_e64 v47, v50, v47, s[10:11]
	ds_bpermute_b32 v50, v46, v47
	s_waitcnt lgkmcnt(2)
	v_add_f32_e32 v51, v48, v51
	s_waitcnt lgkmcnt(1)
	v_add_f32_e32 v49, v22, v49
	v_cndmask_b32_e32 v22, v49, v22, vcc
	ds_bpermute_b32 v49, v43, v22
	s_waitcnt lgkmcnt(1)
	v_add_f32_e32 v50, v47, v50
	v_cndmask_b32_e64 v47, v50, v47, s[12:13]
	ds_bpermute_b32 v50, v21, v47
	v_cndmask_b32_e64 v48, v51, v48, s[14:15]
	s_waitcnt lgkmcnt(1)
	v_add_f32_e32 v49, v22, v49
	v_cndmask_b32_e64 v22, v49, v22, s[6:7]
	ds_bpermute_b32 v49, v44, v22
	ds_bpermute_b32 v51, v25, v23
	s_waitcnt lgkmcnt(2)
	v_add_f32_e32 v50, v47, v50
	v_cndmask_b32_e64 v47, v50, v47, s[14:15]
	ds_write2_b32 v24, v48, v47 offset1:65
	s_waitcnt lgkmcnt(2)
	v_add_f32_e32 v49, v22, v49
	v_cndmask_b32_e64 v22, v49, v22, s[8:9]
	s_waitcnt lgkmcnt(1)
	v_add_f32_e32 v50, v23, v51
	ds_bpermute_b32 v49, v45, v22
	v_cndmask_b32_e32 v23, v50, v23, vcc
	ds_bpermute_b32 v50, v43, v23
	s_waitcnt lgkmcnt(1)
	v_add_f32_e32 v47, v22, v49
	v_cndmask_b32_e64 v47, v47, v22, s[10:11]
	s_waitcnt lgkmcnt(0)
	v_add_f32_e32 v22, v23, v50
	v_cndmask_b32_e64 v49, v22, v23, s[6:7]
	v_add_u32_e32 v50, 0x400, v24
	ds_read2_b32 v[22:23], v50 offset0:4 offset1:69
	ds_bpermute_b32 v51, v44, v49
	ds_bpermute_b32 v48, v46, v47
	s_waitcnt lgkmcnt(2)
	ds_bpermute_b32 v52, v25, v22
	s_waitcnt lgkmcnt(2)
	v_add_f32_e32 v51, v49, v51
	v_cndmask_b32_e64 v49, v51, v49, s[8:9]
	ds_bpermute_b32 v51, v45, v49
	s_waitcnt lgkmcnt(2)
	v_add_f32_e32 v48, v47, v48
	v_cndmask_b32_e64 v47, v48, v47, s[12:13]
	s_waitcnt lgkmcnt(1)
	v_add_f32_e32 v52, v22, v52
	ds_bpermute_b32 v48, v21, v47
	v_cndmask_b32_e32 v22, v52, v22, vcc
	ds_bpermute_b32 v52, v43, v22
	s_waitcnt lgkmcnt(2)
	v_add_f32_e32 v51, v49, v51
	v_cndmask_b32_e64 v49, v51, v49, s[10:11]
	ds_bpermute_b32 v51, v46, v49
	s_waitcnt lgkmcnt(2)
	v_add_f32_e32 v48, v47, v48
	v_cndmask_b32_e64 v47, v48, v47, s[14:15]
	s_waitcnt lgkmcnt(1)
	v_add_f32_e32 v48, v22, v52
	v_cndmask_b32_e64 v22, v48, v22, s[6:7]
	ds_bpermute_b32 v48, v44, v22
	s_waitcnt lgkmcnt(1)
	v_add_f32_e32 v51, v49, v51
	v_cndmask_b32_e64 v49, v51, v49, s[12:13]
	ds_bpermute_b32 v51, v25, v23
	ds_bpermute_b32 v52, v21, v49
	s_waitcnt lgkmcnt(2)
	v_add_f32_e32 v48, v22, v48
	v_cndmask_b32_e64 v22, v48, v22, s[8:9]
	ds_bpermute_b32 v48, v45, v22
	s_waitcnt lgkmcnt(2)
	v_add_f32_e32 v51, v23, v51
	v_cndmask_b32_e32 v23, v51, v23, vcc
	ds_bpermute_b32 v51, v43, v23
	s_waitcnt lgkmcnt(2)
	v_add_f32_e32 v52, v49, v52
	s_waitcnt lgkmcnt(1)
	v_add_f32_e32 v48, v22, v48
	v_cndmask_b32_e64 v22, v48, v22, s[10:11]
	ds_bpermute_b32 v48, v46, v22
	s_waitcnt lgkmcnt(1)
	v_add_f32_e32 v51, v23, v51
	v_cndmask_b32_e64 v23, v51, v23, s[6:7]
	ds_bpermute_b32 v51, v44, v23
	v_cndmask_b32_e64 v49, v52, v49, s[14:15]
	s_waitcnt lgkmcnt(1)
	v_add_f32_e32 v48, v22, v48
	v_cndmask_b32_e64 v48, v48, v22, s[12:13]
	ds_write2_b32 v24, v47, v49 offset0:130 offset1:195
	s_waitcnt lgkmcnt(1)
	v_add_f32_e32 v22, v23, v51
	v_cndmask_b32_e64 v51, v22, v23, s[8:9]
	ds_read2_b32 v[22:23], v50 offset0:134 offset1:199
	ds_bpermute_b32 v52, v21, v48
	ds_bpermute_b32 v53, v45, v51
	s_waitcnt lgkmcnt(2)
	ds_bpermute_b32 v47, v25, v22
	ds_bpermute_b32 v25, v25, v23
	s_waitcnt lgkmcnt(3)
	v_add_f32_e32 v24, v48, v52
	v_cndmask_b32_e64 v24, v24, v48, s[14:15]
	s_waitcnt lgkmcnt(2)
	v_add_f32_e32 v48, v51, v53
	s_waitcnt lgkmcnt(1)
	v_add_f32_e32 v47, v22, v47
	s_waitcnt lgkmcnt(0)
	v_add_f32_e32 v25, v23, v25
	v_cndmask_b32_e32 v22, v47, v22, vcc
	v_cndmask_b32_e32 v23, v25, v23, vcc
	ds_bpermute_b32 v47, v43, v22
	ds_bpermute_b32 v25, v43, v23
	v_cndmask_b32_e64 v48, v48, v51, s[10:11]
	ds_bpermute_b32 v49, v46, v48
	s_waitcnt lgkmcnt(2)
	v_add_f32_e32 v47, v22, v47
	s_waitcnt lgkmcnt(1)
	v_add_f32_e32 v25, v23, v25
	v_cndmask_b32_e64 v22, v47, v22, s[6:7]
	v_cndmask_b32_e64 v23, v25, v23, s[6:7]
	ds_bpermute_b32 v47, v44, v22
	ds_bpermute_b32 v25, v44, v23
	s_waitcnt lgkmcnt(2)
	v_add_f32_e32 v43, v48, v49
	v_cndmask_b32_e64 v43, v43, v48, s[12:13]
	v_readlane_b32 s6, v228, 25
	s_waitcnt lgkmcnt(1)
	v_add_f32_e32 v44, v22, v47
	s_waitcnt lgkmcnt(0)
	v_add_f32_e32 v25, v23, v25
	v_cndmask_b32_e64 v22, v44, v22, s[8:9]
	v_cndmask_b32_e64 v23, v25, v23, s[8:9]
	ds_bpermute_b32 v44, v45, v22
	ds_bpermute_b32 v25, v45, v23
	ds_bpermute_b32 v45, v21, v43
	v_readlane_b32 s7, v228, 26
	s_waitcnt lgkmcnt(2)
	v_add_f32_e32 v44, v22, v44
	s_waitcnt lgkmcnt(1)
	v_add_f32_e32 v25, v23, v25
	v_cndmask_b32_e64 v22, v44, v22, s[10:11]
	v_cndmask_b32_e64 v23, v25, v23, s[10:11]
	ds_bpermute_b32 v44, v46, v22
	ds_bpermute_b32 v25, v46, v23
	s_waitcnt lgkmcnt(2)
	v_add_f32_e32 v45, v43, v45
	s_waitcnt lgkmcnt(1)
	v_add_f32_e32 v44, v22, v44
	s_waitcnt lgkmcnt(0)
	v_add_f32_e32 v25, v23, v25
	v_cndmask_b32_e64 v22, v44, v22, s[12:13]
	v_cndmask_b32_e64 v23, v25, v23, s[12:13]
	ds_bpermute_b32 v44, v21, v22
	ds_bpermute_b32 v21, v21, v23
	v_cndmask_b32_e64 v25, v45, v43, s[14:15]
	ds_write2_b32 v50, v24, v25 offset0:4 offset1:69
	s_waitcnt lgkmcnt(2)
	v_add_f32_e32 v24, v22, v44
	s_waitcnt lgkmcnt(1)
	v_add_f32_e32 v21, v23, v21
	v_cndmask_b32_e64 v22, v24, v22, s[14:15]
	v_cndmask_b32_e64 v21, v21, v23, s[14:15]
	ds_write2_b32 v50, v22, v21 offset0:134 offset1:199
	v_mov_b32_e32 v21, s96
	v_mad_u32_u24 v21, v26, s4, v21
	v_lshl_add_u32 v19, v19, 2, v21
	s_waitcnt lgkmcnt(0)
	s_barrier
	ds_read_b32 v24, v19
	ds_read_b32 v19, v21 offset:252
	s_lshl_b64 s[4:5], s[16:17], 14
	s_add_u32 s4, s6, s4
	s_addc_u32 s5, s7, s5
	v_lshl_add_u32 v28, v28, 2, v21
	s_waitcnt lgkmcnt(0)
	v_sub_f32_e32 v19, v19, v24
	v_mul_f32_e32 v19, 0x3fb8aa3b, v19
	v_exp_f32_e32 v19, v19
	s_lshl_b32 s3, s3, 7
	v_mul_f32_e32 v22, v42, v19
	v_ashrrev_i32_e32 v19, 31, v18
	v_lshl_add_u32 v42, v18, 2, s96
	ds_write_b32 v42, v22 offset:16640
	v_lshl_add_u64 v[22:23], v[18:19], 2, s[4:5]
	global_store_dword v[22:23], v24, off
	v_lshl_add_u32 v24, v29, 2, v21
	ds_read_b32 v24, v24
	ds_read_b32 v25, v21 offset:252
	s_movk_i32 s4, 0x1000
	s_waitcnt lgkmcnt(0)
	v_sub_f32_e32 v25, v25, v24
	v_mul_f32_e32 v25, 0x3fb8aa3b, v25
	v_exp_f32_e32 v25, v25
	s_nop 0
	v_mul_f32_e32 v25, v41, v25
	ds_write_b32 v42, v25 offset:18688
	global_store_dword v[22:23], v24, off offset:2048
	v_lshl_add_u32 v24, v33, 2, v21
	ds_read_b32 v29, v24
	ds_read_b32 v24, v21 offset:252
	s_waitcnt lgkmcnt(0)
	v_sub_f32_e32 v24, v24, v29
	v_mul_f32_e32 v24, 0x3fb8aa3b, v24
	v_exp_f32_e32 v24, v24
	s_nop 0
	v_mul_f32_e32 v24, v40, v24
	ds_write_b32 v42, v24 offset:20736
	v_add_co_u32_e32 v24, vcc, s4, v22
	s_movk_i32 s4, 0x2000
	s_nop 0
	v_addc_co_u32_e32 v25, vcc, 0, v23, vcc
	global_store_dword v[24:25], v29, off
	v_lshl_add_u32 v29, v30, 2, v21
	ds_read_b32 v29, v29
	ds_read_b32 v30, v21 offset:252
	s_waitcnt lgkmcnt(0)
	v_sub_f32_e32 v30, v30, v29
	v_mul_f32_e32 v30, 0x3fb8aa3b, v30
	v_exp_f32_e32 v30, v30
	s_nop 0
	v_mul_f32_e32 v30, v39, v30
	ds_write_b32 v42, v30 offset:22784
	global_store_dword v[24:25], v29, off offset:2048
	v_lshl_add_u32 v24, v32, 2, v21
	ds_read_b32 v29, v24
	ds_read_b32 v24, v21 offset:252
	s_waitcnt lgkmcnt(0)
	v_sub_f32_e32 v24, v24, v29
	v_mul_f32_e32 v24, 0x3fb8aa3b, v24
	v_exp_f32_e32 v24, v24
	s_nop 0
	v_mul_f32_e32 v24, v38, v24
	ds_write_b32 v42, v24 offset:24832
	v_add_co_u32_e32 v24, vcc, s4, v22
	s_movk_i32 s4, 0x3000
	s_nop 0
	v_addc_co_u32_e32 v25, vcc, 0, v23, vcc
	global_store_dword v[24:25], v29, off
	ds_read_b32 v28, v28
	ds_read_b32 v29, v21 offset:252
	s_waitcnt lgkmcnt(0)
	v_sub_f32_e32 v29, v29, v28
	v_mul_f32_e32 v29, 0x3fb8aa3b, v29
	v_exp_f32_e32 v29, v29
	s_nop 0
	v_mul_f32_e32 v29, v37, v29
	ds_write_b32 v42, v29 offset:26880
	global_store_dword v[24:25], v28, off offset:2048
	v_lshl_add_u32 v24, v31, 2, v21
	ds_read_b32 v28, v24
	ds_read_b32 v24, v21 offset:252
	s_waitcnt lgkmcnt(0)
	v_sub_f32_e32 v24, v24, v28
	v_mul_f32_e32 v24, 0x3fb8aa3b, v24
	v_exp_f32_e32 v24, v24
	s_nop 0
	v_mul_f32_e32 v24, v36, v24
	ds_write_b32 v42, v24 offset:28928
	v_add_co_u32_e32 v24, vcc, s4, v22
	v_lshl_add_u32 v22, v27, 2, v21
	s_nop 0
	v_addc_co_u32_e32 v25, vcc, 0, v23, vcc
	global_store_dword v[24:25], v28, off
	ds_read_b32 v23, v22
	ds_read_b32 v21, v21 offset:252
	v_lshrrev_b32_e32 v22, 5, v26
	v_and_b32_e32 v26, 31, v18
	s_lshl_b32 s4, s2, 7
	s_waitcnt lgkmcnt(0)
	v_sub_f32_e32 v21, v21, v23
	v_mul_f32_e32 v21, 0x3fb8aa3b, v21
	v_exp_f32_e32 v21, v21
	s_nop 0
	v_mul_f32_e32 v21, v34, v21
	ds_write_b32 v42, v21 offset:30976
	v_and_b32_e32 v21, 0x3fffff80, v35
	v_lshlrev_b32_e32 v21, 2, v21
	v_add3_u32 v20, s96, v21, v20
	global_store_dword v[24:25], v23, off offset:2048
	ds_write_b128 v20, v[2:5] offset:33024
	ds_write_b128 v20, v[6:9] offset:41216
	ds_write_b128 v20, v[10:13] offset:49408
	ds_write_b128 v20, v[14:17] offset:57600
	v_lshlrev_b32_e32 v2, 9, v22
	v_lshlrev_b32_e32 v20, 2, v26
	v_or3_b32 v2, v2, s3, v20
	v_add_u32_e32 v2, s96, v2
	v_add_u32_e32 v21, 0x8100, v2
	v_lshl_add_u32 v2, v22, 8, s4
	v_or_b32_e32 v2, v2, v20
	v_add_u32_e32 v2, s96, v2
	v_add_u32_e32 v23, 0x4100, v2
	v_mov_b32_e32 v2, 0
	s_mov_b32 s4, s17
	v_mov_b32_e32 v3, v2
	v_mov_b32_e32 v4, v2
	v_mov_b32_e32 v5, v2
	v_mov_b32_e32 v6, v2
	v_mov_b32_e32 v7, v2
	v_mov_b32_e32 v8, v2
	v_mov_b32_e32 v9, v2
	v_mov_b32_e32 v10, v2
	v_mov_b32_e32 v11, v2
	v_mov_b32_e32 v12, v2
	v_mov_b32_e32 v13, v2
	v_mov_b32_e32 v14, v2
	v_mov_b32_e32 v15, v2
	v_mov_b32_e32 v16, v2
	v_mov_b32_e32 v17, v2
	s_waitcnt lgkmcnt(0)
	s_barrier
.LBB0_1632:
	v_add_u32_e32 v28, s4, v23
	ds_read2st64_b32 v[24:25], v28 offset1:2
	ds_read2st64_b32 v[26:27], v21 offset1:4
	s_addk_i32 s4, 0x1000
	s_cmpk_eq_i32 s4, 0x4000
	s_waitcnt lgkmcnt(0)
	v_mfma_f32_32x32x2_f32 v[2:17], v24, v26, v[2:17]
	v_mfma_f32_32x32x2_f32 v[2:17], v25, v27, v[2:17]
	ds_read2st64_b32 v[24:25], v28 offset0:4 offset1:6
	ds_read2st64_b32 v[26:27], v21 offset0:8 offset1:12
	s_waitcnt lgkmcnt(0)
	v_mfma_f32_32x32x2_f32 v[2:17], v24, v26, v[2:17]
	v_mfma_f32_32x32x2_f32 v[2:17], v25, v27, v[2:17]
	ds_read2st64_b32 v[24:25], v28 offset0:8 offset1:10
	ds_read2st64_b32 v[26:27], v21 offset0:16 offset1:20
	s_waitcnt lgkmcnt(0)
	v_mfma_f32_32x32x2_f32 v[2:17], v24, v26, v[2:17]
	v_mfma_f32_32x32x2_f32 v[2:17], v25, v27, v[2:17]
	ds_read2st64_b32 v[24:25], v28 offset0:12 offset1:14
	ds_read2st64_b32 v[26:27], v21 offset0:24 offset1:28
	v_add_u32_e32 v21, 0x2000, v21
	s_waitcnt lgkmcnt(0)
	v_mfma_f32_32x32x2_f32 v[2:17], v24, v26, v[2:17]
	v_mfma_f32_32x32x2_f32 v[2:17], v25, v27, v[2:17]
	s_cbranch_scc0 .LBB0_1632
	s_lshl_b32 s2, s2, 5
	s_lshl_b64 s[6:7], s[16:17], 6
	s_ashr_i32 s5, s2, 31
	s_add_u32 s4, s6, s2
	s_addc_u32 s5, s7, s5
	s_lshl_b64 s[4:5], s[4:5], 9
	v_readlane_b32 s2, v228, 21
	s_add_u32 s2, s2, s4
	v_readlane_b32 s4, v228, 22
	s_addc_u32 s4, s4, s5
	s_add_u32 s2, s2, s3
	s_addc_u32 s3, s4, 0
	v_mov_b32_e32 v21, 0
	v_lshl_add_u64 v[24:25], s[2:3], 0, v[20:21]
	v_lshlrev_b32_e32 v20, 11, v22
	v_lshl_add_u64 v[20:21], v[24:25], 0, v[20:21]
	s_movk_i32 s2, 0x1000
	global_store_dword v[20:21], v2, off
	global_store_dword v[20:21], v3, off offset:512
	global_store_dword v[20:21], v4, off offset:1024
	global_store_dword v[20:21], v5, off offset:1536
	v_add_co_u32_e32 v2, vcc, s2, v20
	s_movk_i32 s2, 0x2000
	s_nop 0
	v_addc_co_u32_e32 v3, vcc, 0, v21, vcc
	global_store_dword v[2:3], v6, off
	global_store_dword v[2:3], v7, off offset:512
	global_store_dword v[2:3], v8, off offset:1024
	global_store_dword v[2:3], v9, off offset:1536
	v_add_co_u32_e32 v2, vcc, s2, v20
	s_nop 1
	v_addc_co_u32_e32 v3, vcc, 0, v21, vcc
	global_store_dword v[2:3], v10, off
	global_store_dword v[2:3], v11, off offset:512
	global_store_dword v[2:3], v12, off offset:1024
	global_store_dword v[2:3], v13, off offset:1536
	v_add_co_u32_e32 v2, vcc, 0x3000, v20
	s_nop 1
	v_addc_co_u32_e32 v3, vcc, 0, v21, vcc
	v_cmp_gt_i32_e32 vcc, 64, v18
	global_store_dword v[2:3], v14, off
	global_store_dword v[2:3], v15, off offset:512
	global_store_dword v[2:3], v16, off offset:1024
	global_store_dword v[2:3], v17, off offset:1536
	s_and_saveexec_b64 s[8:9], vcc
	s_cbranch_execz .LBB0_1635
	s_movk_i32 s2, 0x104
	v_mul_lo_u32 v2, v18, s2
	v_add_u32_e32 v2, s96, v2
	ds_read_b32 v2, v2 offset:252
	s_lshl_b64 s[2:3], s[6:7], 2
	v_readlane_b32 s4, v228, 23
	v_readlane_b32 s5, v228, 24
	s_add_u32 s2, s4, s2
	s_waitcnt lgkmcnt(0)
	v_mul_f32_e32 v2, 0x3fb8aa3b, v2
	v_exp_f32_e32 v4, v2
	s_addc_u32 s3, s5, s3
	v_lshl_add_u64 v[2:3], v[18:19], 2, s[2:3]
	global_store_dword v[2:3], v4, off

.LBB0_1640:
	s_lshr_b32 s16, s2, 2
	s_add_i32 s18, s16, 0x4000
	s_mul_i32 s17, s18, 0x3000
	s_mul_hi_u32 s16, s18, 0x3000
	s_add_u32 s22, s46, s17
	s_addc_u32 s23, s47, s16
	s_waitcnt vmcnt(0)
	s_barrier
	s_and_saveexec_b64 s[16:17], s[6:7]
	s_xor_b64 s[16:17], exec, s[16:17]
	s_cbranch_execz .LBB0_1644
	s_and_saveexec_b64 s[24:25], s[10:11]
	s_cbranch_execz .LBB0_1643
	v_lshl_add_u64 v[42:43], v[4:5], 2, s[22:23]
	global_load_dword v41, v[42:43], off
	s_waitcnt vmcnt(0) lgkmcnt(0)
	ds_write_b32 v6, v41 offset:33280

.LBB0_1644:
	s_andn2_saveexec_b64 s[24:25], s[16:17]
	s_cbranch_execz .LBB0_1648
	v_mov_b64_e32 v[42:43], s[0:1]
	global_load_dwordx2 v[58:59], v[42:43], off offset:152 sc0 sc1
	s_waitcnt vmcnt(0)
	global_load_dwordx2 v[60:61], v[42:43], off offset:160 sc0 sc1
	s_waitcnt vmcnt(0)
	v_mov_b32_e32 v41, s22
	s_mov_b32 s21, s19
	v_mov_b32_e32 v46, s23
	v_add_co_u32_e32 v54, vcc, 0x2000, v41
	v_lshl_add_u64 v[42:43], v[10:11], 2, s[22:23]
	v_lshl_add_u64 v[44:45], v[12:13], 2, s[22:23]
	v_addc_co_u32_e32 v55, vcc, 0, v46, vcc
	global_load_dword v41, v[42:43], off
	global_load_dword v66, v[44:45], off
	s_nop 0
	global_load_dwordx4 v[42:45], v[54:55], off offset:1120
	global_load_dwordx4 v[46:49], v[54:55], off offset:1136
	global_load_dwordx4 v[50:53], v[54:55], off offset:1152
	s_nop 0
	global_load_dwordx4 v[54:57], v[54:55], off offset:1168
	v_xor_b32_e32 v80, 32, v1
	s_waitcnt lgkmcnt(0)
	v_lshl_add_u64 v[58:59], v[58:59], 0, s[20:21]
	v_lshl_add_u64 v[60:61], v[8:9], 2, v[60:61]
	v_lshl_add_u64 v[58:59], v[130:131], 2, v[58:59]
	global_load_dword v67, v[60:61], off
	global_load_dword v68, v[58:59], off
	global_load_dword v69, v[58:59], off offset:1024
	global_load_dword v70, v[58:59], off offset:2048
	global_load_dword v71, v[58:59], off offset:3072
	v_add_co_u32_e64 v62, s[16:17], s30, v58
	v_add_co_u32_e32 v60, vcc, s31, v58
	s_nop 0
	v_addc_co_u32_e64 v63, s[16:17], 0, v59, s[16:17]
	v_add_co_u32_e64 v64, s[16:17], s29, v58
	v_addc_co_u32_e32 v61, vcc, 0, v59, vcc
	s_nop 0
	v_addc_co_u32_e64 v65, s[16:17], 0, v59, s[16:17]
	global_load_dword v58, v[62:63], off offset:-4096
	global_load_dword v59, v[60:61], off offset:1024
	global_load_dword v72, v[60:61], off offset:2048
	s_nop 0
	global_load_dword v60, v[60:61], off offset:3072
	s_nop 0
	global_load_dword v61, v[62:63], off
	global_load_dword v73, v[62:63], off offset:1024
	global_load_dword v74, v[62:63], off offset:2048
	s_nop 0
	global_load_dword v62, v[62:63], off offset:3072
	s_nop 0
	global_load_dword v63, v[64:65], off
	global_load_dword v75, v[64:65], off offset:1024
	global_load_dword v76, v[64:65], off offset:2048
	s_nop 0
	global_load_dword v64, v[64:65], off offset:3072
	v_cmp_lt_i32_e32 vcc, v36, v35
	s_waitcnt vmcnt(0)
	v_mul_f32_e32 v77, 0x3e000000, v41
	v_mul_f32_e32 v41, v77, v66
	v_cndmask_b32_e32 v65, v1, v36, vcc
	v_lshlrev_b32_e32 v65, 2, v65
	ds_bpermute_b32 v41, v65, v41
	v_cmp_lt_i32_e32 vcc, v37, v35
	s_waitcnt lgkmcnt(0)
	v_fmac_f32_e32 v41, v77, v66
	v_cndmask_b32_e32 v65, v1, v37, vcc
	v_lshlrev_b32_e32 v65, 2, v65
	ds_bpermute_b32 v65, v65, v41
	v_cmp_lt_i32_e32 vcc, v38, v35
	s_waitcnt lgkmcnt(0)
	v_add_f32_e32 v41, v41, v65
	v_cndmask_b32_e32 v78, v1, v38, vcc
	v_cmp_lt_i32_e32 vcc, v39, v35
	v_lshlrev_b32_e32 v78, 2, v78
	ds_bpermute_b32 v65, v78, v41
	v_cndmask_b32_e32 v79, v1, v39, vcc
	v_cmp_lt_i32_e32 vcc, v40, v35
	v_lshlrev_b32_e32 v79, 2, v79
	s_waitcnt lgkmcnt(0)
	v_add_f32_e32 v41, v41, v65
	v_cndmask_b32_e32 v78, v1, v40, vcc
	v_cmp_lt_i32_e32 vcc, v80, v35
	ds_bpermute_b32 v65, v79, v41
	v_lshlrev_b32_e32 v78, 2, v78
	s_waitcnt lgkmcnt(0)
	v_add_f32_e32 v41, v41, v65
	v_fmac_f32_e32 v67, v42, v68
	v_fmac_f32_e32 v67, v43, v69
	v_fmac_f32_e32 v67, v44, v70
	v_fmac_f32_e32 v67, v45, v71
	v_cndmask_b32_e32 v43, v1, v80, vcc
	v_fmac_f32_e32 v67, v46, v58
	v_fmac_f32_e32 v67, v47, v59
	v_fmac_f32_e32 v67, v48, v72
	v_fmac_f32_e32 v67, v49, v60
	v_fmac_f32_e32 v67, v50, v61
	v_fmac_f32_e32 v67, v51, v73
	v_fmac_f32_e32 v67, v52, v74
	v_fmac_f32_e32 v67, v53, v62
	v_fmac_f32_e32 v67, v54, v63
	v_fmac_f32_e32 v67, v55, v75
	v_fmac_f32_e32 v67, v56, v76
	v_fmac_f32_e32 v67, v57, v64
	v_mul_f32_e64 v42, |v67|, s33
	v_exp_f32_e32 v42, v42
	v_min_f32_e32 v45, 0, v67
	v_lshlrev_b32_e32 v43, 2, v43
	v_add_f32_e32 v42, 1.0, v42
	v_cmp_gt_f32_e32 vcc, s34, v42
	s_nop 1
	v_cndmask_b32_e64 v44, 0, 32, vcc
	v_ldexp_f32 v42, v42, v44
	v_log_f32_e32 v42, v42
	ds_bpermute_b32 v44, v78, v41
	v_cndmask_b32_e32 v46, 0, v34, vcc
	v_mul_f32_e32 v47, 0x3f317217, v42
	v_fma_f32 v47, v42, s35, -v47
	v_fmac_f32_e32 v47, 0x3377d1cf, v42
	v_fmac_f32_e32 v47, 0x3f317217, v42
	v_cmp_lt_f32_e64 vcc, |v42|, s36
	s_waitcnt lgkmcnt(0)
	v_add_f32_e32 v41, v41, v44
	v_cndmask_b32_e32 v42, v42, v47, vcc
	v_sub_f32_e32 v42, v42, v46
	v_sub_f32_e32 v42, v45, v42
	v_mul_f32_e32 v42, 0x3d800000, v42
	v_mul_f32_e32 v42, 0x3fb8aa3b, v42
	v_exp_f32_e32 v45, v42
	ds_bpermute_b32 v42, v43, v41
	v_mul_f32_e32 v43, v77, v45
	ds_write2st64_b32 v6, v43, v66 offset0:128 offset1:129
	ds_write_b32 v6, v45 offset:33280
	s_and_saveexec_b64 s[16:17], s[12:13]
	s_cbranch_execz .LBB0_1647
	s_waitcnt lgkmcnt(2)
	v_add_f32_e32 v41, v41, v42
	v_mov_b32_e32 v42, s96
	ds_write_b32 v42, v41 offset:34048

.LBB0_1648:
	s_or_b64 exec, exec, s[24:25]
	s_waitcnt lgkmcnt(0)
	v_mov_b64_e32 v[42:43], s[0:1]
	s_waitcnt lgkmcnt(0)
	s_barrier
	global_load_dwordx2 v[42:43], v[42:43], off offset:56 sc0 sc1
	s_waitcnt vmcnt(0)
	s_and_b32 s16, s2, 0x7ffffffc
	s_mov_b32 s17, s19
	s_or_b32 s16, s4, s16
	s_lshl_b64 s[16:17], s[16:17], 15
	v_mov_b32_e32 v41, 0
	s_waitcnt lgkmcnt(0)
	v_lshl_add_u64 v[50:51], v[42:43], 0, s[16:17]
	v_lshl_add_u64 v[42:43], v[50:51], 0, v[18:19]
	global_load_dwordx4 v[42:45], v[42:43], off
	s_add_u32 s16, s5, s16
	s_addc_u32 s17, s26, s17
	v_lshl_add_u64 v[54:55], s[16:17], 0, v[18:19]
	v_lshl_add_u64 v[56:57], v[50:51], 0, v[20:21]
	s_waitcnt vmcnt(0)
	ds_write_b128 v2, v[42:45]
	ds_read_b128 v[46:49], v3 offset:33536
	ds_read2st64_b32 v[52:53], v26 offset0:129 offset1:130
	s_waitcnt lgkmcnt(0)
	v_pk_mul_f32 v[48:49], v[48:49], v[52:53] op_sel_hi:[1,0]
	v_pk_mul_f32 v[46:47], v[46:47], v[52:53] op_sel_hi:[1,0]
	v_mov_b32_e32 v52, v53
	v_pk_fma_f32 v[44:45], v[44:45], v[52:53], v[48:49] op_sel_hi:[1,0,1]
	v_pk_fma_f32 v[42:43], v[42:43], v[52:53], v[46:47] op_sel_hi:[1,0,1]
	global_store_dwordx4 v[54:55], v[42:45], off
	global_load_dwordx4 v[42:45], v[56:57], off
	v_lshl_add_u64 v[54:55], s[16:17], 0, v[20:21]
	v_lshl_add_u64 v[56:57], v[50:51], 0, v[22:23]
	v_lshl_add_u64 v[50:51], v[50:51], 0, v[24:25]
	s_waitcnt vmcnt(0)
	ds_write_b128 v7, v[42:45]
	ds_read_b128 v[46:49], v3 offset:33536
	ds_read2st64_b32 v[52:53], v27 offset0:129 offset1:130
	s_waitcnt lgkmcnt(0)
	v_pk_mul_f32 v[48:49], v[48:49], v[52:53] op_sel_hi:[1,0]
	v_pk_mul_f32 v[46:47], v[46:47], v[52:53] op_sel_hi:[1,0]
	v_mov_b32_e32 v52, v53
	v_pk_fma_f32 v[44:45], v[44:45], v[52:53], v[48:49] op_sel_hi:[1,0,1]
	v_pk_fma_f32 v[42:43], v[42:43], v[52:53], v[46:47] op_sel_hi:[1,0,1]
	global_store_dwordx4 v[54:55], v[42:45], off
	global_load_dwordx4 v[42:45], v[56:57], off
	v_lshl_add_u64 v[54:55], s[16:17], 0, v[22:23]
	s_waitcnt vmcnt(0)
	ds_write_b128 v30, v[42:45]
	ds_read_b128 v[46:49], v3 offset:33536
	ds_read2st64_b32 v[52:53], v28 offset0:129 offset1:130
	s_waitcnt lgkmcnt(0)
	v_pk_mul_f32 v[48:49], v[48:49], v[52:53] op_sel_hi:[1,0]
	v_pk_mul_f32 v[46:47], v[46:47], v[52:53] op_sel_hi:[1,0]
	v_mov_b32_e32 v52, v53
	v_pk_fma_f32 v[44:45], v[44:45], v[52:53], v[48:49] op_sel_hi:[1,0,1]
	v_pk_fma_f32 v[42:43], v[42:43], v[52:53], v[46:47] op_sel_hi:[1,0,1]
	global_store_dwordx4 v[54:55], v[42:45], off
	global_load_dwordx4 v[42:45], v[50:51], off
	v_lshl_add_u64 v[52:53], s[16:17], 0, v[24:25]
	s_waitcnt vmcnt(0)
	ds_write_b128 v31, v[42:45]
	ds_read_b128 v[46:49], v3 offset:33536
	ds_read2st64_b32 v[50:51], v29 offset0:129 offset1:130
	s_waitcnt lgkmcnt(0)
	v_pk_mul_f32 v[48:49], v[48:49], v[50:51] op_sel_hi:[1,0]
	v_pk_mul_f32 v[46:47], v[46:47], v[50:51] op_sel_hi:[1,0]
	v_mov_b32_e32 v50, v51
	v_pk_fma_f32 v[44:45], v[44:45], v[50:51], v[48:49] op_sel_hi:[1,0,1]
	v_pk_fma_f32 v[42:43], v[42:43], v[50:51], v[46:47] op_sel_hi:[1,0,1]
	global_store_dwordx4 v[52:53], v[42:45], off
	s_waitcnt lgkmcnt(0)
	s_barrier
	s_and_saveexec_b64 s[16:17], s[8:9]
	s_cbranch_execz .LBB0_1654
	v_mov_b32_e32 v41, 0
	s_mov_b32 s21, 0
	s_mov_b32 s24, s28

.LBB0_1654:
	s_or_b64 exec, exec, s[16:17]
	s_waitcnt lgkmcnt(0)
	s_barrier
	s_and_saveexec_b64 s[24:25], s[8:9]
	s_cbranch_execz .LBB0_1639
	v_mov_b32_e32 v42, s37
	v_mov_b64_e32 v[44:45], s[0:1]
	ds_read2_b32 v[42:43], v42 offset1:1
	global_load_dwordx2 v[44:45], v[44:45], off offset:168 sc0 sc1
	s_waitcnt vmcnt(0)
	v_lshl_add_u64 v[46:47], v[14:15], 2, s[22:23]
	global_load_dword v46, v[46:47], off
	s_waitcnt lgkmcnt(0)
	v_add_f32_e32 v42, v42, v43
	v_fmamk_f32 v42, v42, 0x3c000000, v32
	v_mul_f32_e32 v43, 0x4f800000, v42
	v_cmp_gt_f32_e32 vcc, s41, v42
	v_lshl_add_u64 v[44:45], v[130:131], 2, v[44:45]
	global_load_dword v44, v[44:45], off
	v_cndmask_b32_e32 v42, v42, v43, vcc
	v_sqrt_f32_e32 v43, v42
	s_nop 0
	v_add_u32_e32 v45, -1, v43
	v_add_u32_e32 v47, 1, v43
	v_fma_f32 v48, -v45, v43, v42
	v_fma_f32 v49, -v47, v43, v42
	v_cmp_ge_f32_e64 s[16:17], 0, v48
	s_nop 1
	v_cndmask_b32_e64 v43, v43, v45, s[16:17]
	v_cmp_lt_f32_e64 s[16:17], 0, v49
	s_nop 1
	v_cndmask_b32_e64 v43, v43, v47, s[16:17]
	v_mul_f32_e32 v45, 0x37800000, v43
	v_cndmask_b32_e32 v43, v43, v45, vcc
	v_cmp_class_f32_e32 vcc, v42, v33
	s_nop 1
	v_cndmask_b32_e32 v42, v43, v42, vcc
	v_div_scale_f32 v43, s[16:17], v42, v42, 1.0
	v_rcp_f32_e32 v45, v43
	v_div_scale_f32 v47, vcc, 1.0, v42, 1.0
	s_lshl_b64 s[16:17], s[18:19], 11
	v_fma_f32 v48, -v43, v45, 1.0
	v_fmac_f32_e32 v45, v48, v45
	v_mul_f32_e32 v48, v47, v45
	v_fma_f32 v49, -v43, v48, v47
	v_fmac_f32_e32 v48, v49, v45
	v_fma_f32 v43, -v43, v48, v47
	s_waitcnt vmcnt(0)
	v_mul_f32_e32 v47, 0xbfb8aa3b, v46
	v_exp_f32_e32 v47, v47
	v_div_fmas_f32 v43, v43, v45, v48
	v_div_fixup_f32 v42, v43, v42, 1.0
	v_mul_f32_e32 v41, v41, v42
	v_add_f32_e32 v43, 1.0, v47
	v_div_scale_f32 v45, s[22:23], v43, v43, v46
	v_rcp_f32_e32 v47, v45
	v_div_scale_f32 v42, vcc, v46, v43, v46
	v_fma_f32 v48, -v45, v47, 1.0
	v_fmac_f32_e32 v47, v48, v47
	v_mul_f32_e32 v48, v42, v47
	v_fma_f32 v49, -v45, v48, v42
	v_fmac_f32_e32 v48, v49, v47
	v_fma_f32 v42, -v45, v48, v42
	v_div_fmas_f32 v42, v42, v47, v48
	v_div_fixup_f32 v42, v42, v43, v46
	v_mul_f32_e32 v41, v44, v41
	v_mul_f32_e32 v41, v41, v42
	v_bfe_u32 v42, v41, 16, 1
	v_add3_u32 v41, v41, v42, s44
	v_lshl_add_u64 v[42:43], v[16:17], 0, s[16:17]
	global_store_short_d16_hi v[42:43], v41, off
	s_branch .LBB0_1639

.LBB0_1711:
	s_cmp_lt_i32 s90, 9
	s_cselect_b64 s[4:5], -1, 0
	s_cmp_gt_i32 s91, 8
	s_cselect_b64 s[6:7], -1, 0
	s_and_b64 s[4:5], s[4:5], s[6:7]
	s_andn2_b64 vcc, exec, s[4:5]
	s_cbranch_vccnz .LBB0_2258
	s_add_u32 s2, s38, 0x31600000
	s_addc_u32 s4, s39, 0
	s_cmp_gt_i32 s40, 15
	s_cselect_b64 s[6:7], -1, 0
	s_and_b32 s5, s40, 6
	s_cmp_eq_u32 s5, 6
	s_cselect_b64 s[8:9], -1, 0
	s_ashr_i32 s41, s40, 31
	s_or_b64 s[14:15], s[6:7], s[8:9]
	s_lshl_b32 s8, s3, 5
	s_lshl_b64 s[6:7], s[40:41], 18
	s_add_u32 s26, s2, s6
	s_addc_u32 s27, s4, s7
	s_add_u32 s16, s26, 0x80000
	s_addc_u32 s17, s27, 0
	s_ashr_i32 s9, s8, 31
	s_lshl_b64 s[6:7], s[8:9], 10
	s_add_u32 s6, s26, s6
	s_addc_u32 s7, s27, s7
	s_add_u32 s5, s6, 0x800
	s_addc_u32 s9, s7, 0
	v_mov_b32_e32 v133, 0
	s_and_b64 s[10:11], s[14:15], exec
	s_cselect_b32 s10, s6, s16
	s_cselect_b32 s11, s7, s17
	s_cmp_lt_i32 s3, 8
	v_lshlrev_b64 v[24:25], 2, v[132:133]
	s_cselect_b32 s11, s9, s11
	s_cselect_b32 s10, s5, s10
	v_lshl_add_u64 v[2:3], s[6:7], 0, v[24:25]
	s_or_b32 s6, s8, 1
	s_ashr_i32 s7, s6, 31
	global_load_dword v20, v[2:3], off
	global_load_dword v21, v[2:3], off offset:256
	v_lshl_add_u64 v[2:3], s[10:11], 0, v[24:25]
	s_lshl_b64 s[10:11], s[6:7], 10
	s_add_u32 s10, s26, s10
	s_addc_u32 s11, s27, s11
	s_add_u32 s5, s10, 0x800
	s_addc_u32 s7, s11, 0
	s_add_u32 s9, s26, 0x80400
	s_addc_u32 s28, s27, 0
	s_and_b64 s[12:13], s[14:15], exec
	s_cselect_b32 s12, s10, s9
	s_cselect_b32 s13, s11, s28
	s_cmpk_lt_i32 s6, 0xfe
	s_cselect_b32 s7, s7, s13
	s_cselect_b32 s6, s5, s12
	s_or_b32 s90, s8, 2
	global_load_dword v22, v[2:3], off offset:512
	global_load_dword v23, v[2:3], off offset:768
	v_lshl_add_u64 v[2:3], s[10:11], 0, v[24:25]
	s_ashr_i32 s91, s90, 31
	global_load_dword v107, v[2:3], off
	global_load_dword v105, v[2:3], off offset:256
	v_lshl_add_u64 v[2:3], s[6:7], 0, v[24:25]
	s_lshl_b64 s[6:7], s[90:91], 10
	s_add_u32 s6, s26, s6
	s_addc_u32 s7, s27, s7
	s_add_u32 s5, s6, 0x800
	s_addc_u32 s12, s7, 0
	s_and_b64 s[10:11], s[14:15], exec
	s_cselect_b32 s10, s6, s16
	s_cselect_b32 s11, s7, s17
	s_cmpk_lt_i32 s90, 0xfe
	s_cselect_b32 s11, s12, s11
	s_cselect_b32 s10, s5, s10
	s_or_b32 s88, s8, 3
	s_ashr_i32 s89, s88, 31
	global_load_dword v108, v[2:3], off offset:512
	global_load_dword v106, v[2:3], off offset:768
	v_lshl_add_u64 v[2:3], s[6:7], 0, v[24:25]
	s_lshl_b64 s[6:7], s[88:89], 10
	s_add_u32 s6, s26, s6
	s_addc_u32 s7, s27, s7
	s_add_u32 s5, s6, 0x800
	s_addc_u32 s12, s7, 0
	global_load_dword v103, v[2:3], off
	global_load_dword v100, v[2:3], off offset:256
	v_lshl_add_u64 v[2:3], s[10:11], 0, v[24:25]
	s_and_b64 s[10:11], s[14:15], exec
	s_cselect_b32 s10, s6, s9
	s_cselect_b32 s11, s7, s28
	s_cmpk_lt_i32 s88, 0xfe
	s_cselect_b32 s11, s12, s11
	s_cselect_b32 s10, s5, s10
	s_or_b32 s86, s8, 4
	s_ashr_i32 s87, s86, 31
	global_load_dword v104, v[2:3], off offset:512
	global_load_dword v102, v[2:3], off offset:768
	v_lshl_add_u64 v[2:3], s[6:7], 0, v[24:25]
	s_lshl_b64 s[6:7], s[86:87], 10
	s_add_u32 s6, s26, s6
	s_addc_u32 s7, s27, s7
	s_add_u32 s5, s6, 0x800
	s_addc_u32 s12, s7, 0
	global_load_dword v98, v[2:3], off
	global_load_dword v97, v[2:3], off offset:256
	v_lshl_add_u64 v[2:3], s[10:11], 0, v[24:25]
	s_and_b64 s[10:11], s[14:15], exec
	s_cselect_b32 s10, s6, s16
	s_cselect_b32 s11, s7, s17
	s_cmpk_lt_i32 s86, 0xfe
	s_cselect_b32 s11, s12, s11
	s_cselect_b32 s10, s5, s10
	s_or_b32 s84, s8, 5
	s_ashr_i32 s85, s84, 31
	global_load_dword v101, v[2:3], off offset:512
	global_load_dword v99, v[2:3], off offset:768
	v_lshl_add_u64 v[2:3], s[6:7], 0, v[24:25]
	s_lshl_b64 s[6:7], s[84:85], 10
	s_add_u32 s6, s26, s6
	s_addc_u32 s7, s27, s7
	s_add_u32 s5, s6, 0x800
	s_addc_u32 s12, s7, 0
	global_load_dword v94, v[2:3], off
	global_load_dword v93, v[2:3], off offset:256
	v_lshl_add_u64 v[2:3], s[10:11], 0, v[24:25]
	s_and_b64 s[10:11], s[14:15], exec
	s_cselect_b32 s10, s6, s9
	s_cselect_b32 s11, s7, s28
	s_cmpk_lt_i32 s84, 0xfe
	s_cselect_b32 s11, s12, s11
	s_cselect_b32 s10, s5, s10
	s_or_b32 s82, s8, 6
	s_ashr_i32 s83, s82, 31
	global_load_dword v96, v[2:3], off offset:512
	global_load_dword v95, v[2:3], off offset:768
	v_lshl_add_u64 v[2:3], s[6:7], 0, v[24:25]
	s_lshl_b64 s[6:7], s[82:83], 10
	s_add_u32 s6, s26, s6
	s_addc_u32 s7, s27, s7
	s_add_u32 s5, s6, 0x800
	s_addc_u32 s12, s7, 0
	global_load_dword v90, v[2:3], off
	global_load_dword v89, v[2:3], off offset:256
	v_lshl_add_u64 v[2:3], s[10:11], 0, v[24:25]
	s_and_b64 s[10:11], s[14:15], exec
	s_cselect_b32 s10, s6, s16
	s_cselect_b32 s11, s7, s17
	s_cmpk_lt_i32 s82, 0xfe
	s_cselect_b32 s11, s12, s11
	s_cselect_b32 s10, s5, s10
	s_or_b32 s80, s8, 7
	s_ashr_i32 s81, s80, 31
	global_load_dword v92, v[2:3], off offset:512
	global_load_dword v91, v[2:3], off offset:768
	v_lshl_add_u64 v[2:3], s[6:7], 0, v[24:25]
	s_lshl_b64 s[6:7], s[80:81], 10
	s_add_u32 s6, s26, s6
	s_addc_u32 s7, s27, s7
	s_add_u32 s5, s6, 0x800
	s_addc_u32 s12, s7, 0
	global_load_dword v87, v[2:3], off
	global_load_dword v85, v[2:3], off offset:256
	v_lshl_add_u64 v[2:3], s[10:11], 0, v[24:25]
	s_and_b64 s[10:11], s[14:15], exec
	s_cselect_b32 s10, s6, s9
	s_cselect_b32 s11, s7, s28
	s_cmpk_lt_i32 s80, 0xfe
	s_cselect_b32 s11, s12, s11
	s_cselect_b32 s10, s5, s10
	s_or_b32 s78, s8, 8
	s_ashr_i32 s79, s78, 31
	global_load_dword v88, v[2:3], off offset:512
	global_load_dword v86, v[2:3], off offset:768
	v_lshl_add_u64 v[2:3], s[6:7], 0, v[24:25]
	s_lshl_b64 s[6:7], s[78:79], 10
	s_add_u32 s6, s26, s6
	s_addc_u32 s7, s27, s7
	s_add_u32 s5, s6, 0x800
	s_addc_u32 s12, s7, 0
	global_load_dword v82, v[2:3], off
	global_load_dword v81, v[2:3], off offset:256
	v_lshl_add_u64 v[2:3], s[10:11], 0, v[24:25]
	s_and_b64 s[10:11], s[14:15], exec
	s_cselect_b32 s10, s6, s16
	s_cselect_b32 s11, s7, s17
	s_cmpk_lt_i32 s78, 0xfe
	s_cselect_b32 s11, s12, s11
	s_cselect_b32 s10, s5, s10
	s_or_b32 s76, s8, 9
	s_ashr_i32 s77, s76, 31
	global_load_dword v84, v[2:3], off offset:512
	global_load_dword v83, v[2:3], off offset:768
	v_lshl_add_u64 v[2:3], s[6:7], 0, v[24:25]
	s_lshl_b64 s[6:7], s[76:77], 10
	s_add_u32 s6, s26, s6
	s_addc_u32 s7, s27, s7
	s_add_u32 s5, s6, 0x800
	s_addc_u32 s12, s7, 0
	global_load_dword v79, v[2:3], off
	global_load_dword v77, v[2:3], off offset:256
	v_lshl_add_u64 v[2:3], s[10:11], 0, v[24:25]
	s_and_b64 s[10:11], s[14:15], exec
	s_cselect_b32 s10, s6, s9
	s_cselect_b32 s11, s7, s28
	s_cmpk_lt_i32 s76, 0xfe
	s_cselect_b32 s11, s12, s11
	s_cselect_b32 s10, s5, s10
	s_or_b32 s74, s8, 10
	s_ashr_i32 s75, s74, 31
	global_load_dword v80, v[2:3], off offset:512
	global_load_dword v78, v[2:3], off offset:768
	v_lshl_add_u64 v[2:3], s[6:7], 0, v[24:25]
	s_lshl_b64 s[6:7], s[74:75], 10
	s_add_u32 s6, s26, s6
	s_addc_u32 s7, s27, s7
	s_add_u32 s5, s6, 0x800
	s_addc_u32 s12, s7, 0
	global_load_dword v73, v[2:3], off
	global_load_dword v72, v[2:3], off offset:256
	v_lshl_add_u64 v[2:3], s[10:11], 0, v[24:25]
	s_and_b64 s[10:11], s[14:15], exec
	s_cselect_b32 s10, s6, s16
	s_cselect_b32 s11, s7, s17
	s_cmpk_lt_i32 s74, 0xfe
	s_cselect_b32 s11, s12, s11
	s_cselect_b32 s10, s5, s10
	s_or_b32 s70, s8, 11
	s_ashr_i32 s71, s70, 31
	global_load_dword v76, v[2:3], off offset:512
	global_load_dword v74, v[2:3], off offset:768
	v_lshl_add_u64 v[2:3], s[6:7], 0, v[24:25]
	s_lshl_b64 s[6:7], s[70:71], 10
	s_add_u32 s6, s26, s6
	s_addc_u32 s7, s27, s7
	s_add_u32 s5, s6, 0x800
	s_addc_u32 s12, s7, 0
	global_load_dword v70, v[2:3], off
	global_load_dword v68, v[2:3], off offset:256
	v_lshl_add_u64 v[2:3], s[10:11], 0, v[24:25]
	s_and_b64 s[10:11], s[14:15], exec
	s_cselect_b32 s10, s6, s9
	s_cselect_b32 s11, s7, s28
	s_cmpk_lt_i32 s70, 0xfe
	s_cselect_b32 s11, s12, s11
	s_cselect_b32 s10, s5, s10
	s_or_b32 s66, s8, 12
	s_ashr_i32 s67, s66, 31
	global_load_dword v71, v[2:3], off offset:512
	global_load_dword v69, v[2:3], off offset:768
	v_lshl_add_u64 v[2:3], s[6:7], 0, v[24:25]
	s_lshl_b64 s[6:7], s[66:67], 10
	s_add_u32 s6, s26, s6
	s_addc_u32 s7, s27, s7
	s_add_u32 s5, s6, 0x800
	s_addc_u32 s12, s7, 0
	global_load_dword v65, v[2:3], off
	global_load_dword v64, v[2:3], off offset:256
	v_lshl_add_u64 v[2:3], s[10:11], 0, v[24:25]
	s_and_b64 s[10:11], s[14:15], exec
	s_cselect_b32 s10, s6, s16
	s_cselect_b32 s11, s7, s17
	s_cmpk_lt_i32 s66, 0xfe
	s_cselect_b32 s11, s12, s11
	s_cselect_b32 s10, s5, s10
	s_or_b32 s64, s8, 13
	s_ashr_i32 s65, s64, 31
	global_load_dword v67, v[2:3], off offset:512
	global_load_dword v66, v[2:3], off offset:768
	v_lshl_add_u64 v[2:3], s[6:7], 0, v[24:25]
	s_lshl_b64 s[6:7], s[64:65], 10
	s_add_u32 s6, s26, s6
	s_addc_u32 s7, s27, s7
	s_add_u32 s5, s6, 0x800
	s_addc_u32 s12, s7, 0
	global_load_dword v62, v[2:3], off
	global_load_dword v60, v[2:3], off offset:256
	v_lshl_add_u64 v[2:3], s[10:11], 0, v[24:25]
	s_and_b64 s[10:11], s[14:15], exec
	s_cselect_b32 s10, s6, s9
	s_cselect_b32 s11, s7, s28
	s_cmpk_lt_i32 s64, 0xfe
	global_load_dword v63, v[2:3], off offset:512
	global_load_dword v61, v[2:3], off offset:768
	s_cselect_b32 s11, s12, s11
	s_cselect_b32 s10, s5, s10
	v_lshl_add_u64 v[2:3], s[6:7], 0, v[24:25]
	global_load_dword v56, v[2:3], off
	global_load_dword v55, v[2:3], off offset:256
	v_lshl_add_u64 v[2:3], s[10:11], 0, v[24:25]
	s_or_b32 s10, s8, 14
	s_ashr_i32 s11, s10, 31
	s_lshl_b64 s[6:7], s[10:11], 10
	s_add_u32 s6, s26, s6
	s_addc_u32 s7, s27, s7
	s_add_u32 s5, s6, 0x800
	s_addc_u32 s11, s7, 0
	s_and_b64 s[12:13], s[14:15], exec
	s_cselect_b32 s12, s6, s16
	s_cselect_b32 s13, s7, s17
	s_cmpk_lt_i32 s10, 0xfe
	global_load_dword v59, v[2:3], off offset:512
	global_load_dword v57, v[2:3], off offset:768
	s_cselect_b32 s13, s11, s13
	s_cselect_b32 s12, s5, s12
	v_lshl_add_u64 v[2:3], s[6:7], 0, v[24:25]
	s_or_b32 s6, s8, 15
	s_ashr_i32 s7, s6, 31
	global_load_dword v53, v[2:3], off
	global_load_dword v51, v[2:3], off offset:256
	v_lshl_add_u64 v[2:3], s[12:13], 0, v[24:25]
	s_lshl_b64 s[12:13], s[6:7], 10
	s_add_u32 s12, s26, s12
	s_addc_u32 s13, s27, s13
	s_add_u32 s5, s12, 0x800
	s_addc_u32 s7, s13, 0
	s_and_b64 s[18:19], s[14:15], exec
	s_cselect_b32 s11, s12, s9
	s_cselect_b32 s18, s13, s28
	s_cmpk_lt_i32 s6, 0xfe
	global_load_dword v54, v[2:3], off offset:512
	global_load_dword v52, v[2:3], off offset:768
	s_cselect_b32 s19, s7, s18
	s_cselect_b32 s18, s5, s11
	v_lshl_add_u64 v[2:3], s[12:13], 0, v[24:25]
	s_or_b32 s12, s8, 16
	s_ashr_i32 s13, s12, 31
	global_load_dword v49, v[2:3], off
	global_load_dword v1, v[2:3], off offset:256
	v_lshl_add_u64 v[2:3], s[18:19], 0, v[24:25]
	s_and_b32 s5, s40, 1
	s_lshl_b64 s[18:19], s[12:13], 10
	s_add_u32 s18, s26, s18
	s_addc_u32 s19, s27, s19
	s_add_u32 s7, s18, 0x800
	s_addc_u32 s11, s19, 0
	s_and_b64 s[20:21], s[14:15], exec
	s_cselect_b32 s13, s18, s16
	s_cselect_b32 s20, s19, s17
	s_cmpk_lt_i32 s12, 0xfe
	s_cselect_b32 s21, s11, s20
	s_cselect_b32 s20, s7, s13
	s_or_b32 s62, s8, 17
	s_ashr_i32 s63, s62, 31
	global_load_dword v50, v[2:3], off offset:512
	global_load_dword v48, v[2:3], off offset:768
	v_lshl_add_u64 v[2:3], s[18:19], 0, v[24:25]
	s_lshl_b64 s[18:19], s[62:63], 10
	s_add_u32 s18, s26, s18
	s_addc_u32 s19, s27, s19
	s_add_u32 s7, s18, 0x800
	s_addc_u32 s11, s19, 0
	global_load_dword v38, v[2:3], off
	global_load_dword v39, v[2:3], off offset:256
	v_lshl_add_u64 v[2:3], s[20:21], 0, v[24:25]
	s_and_b64 s[20:21], s[14:15], exec
	s_cselect_b32 s13, s18, s9
	s_cselect_b32 s20, s19, s28
	s_cmpk_lt_i32 s62, 0xfe
	s_cselect_b32 s21, s11, s20
	s_cselect_b32 s20, s7, s13
	s_or_b32 s60, s8, 18
	s_ashr_i32 s61, s60, 31
	global_load_dword v36, v[2:3], off offset:512
	global_load_dword v37, v[2:3], off offset:768
	v_lshl_add_u64 v[2:3], s[18:19], 0, v[24:25]
	s_lshl_b64 s[18:19], s[60:61], 10
	s_add_u32 s18, s26, s18
	s_addc_u32 s19, s27, s19
	s_add_u32 s7, s18, 0x800
	s_addc_u32 s11, s19, 0
	global_load_dword v177, v[2:3], off
	global_load_dword v175, v[2:3], off offset:256
	v_lshl_add_u64 v[2:3], s[20:21], 0, v[24:25]
	s_and_b64 s[20:21], s[14:15], exec
	s_cselect_b32 s13, s18, s16
	s_cselect_b32 s20, s19, s17
	s_cmpk_lt_i32 s60, 0xfe
	s_cselect_b32 s21, s11, s20
	s_cselect_b32 s20, s7, s13
	s_or_b32 s58, s8, 19
	s_ashr_i32 s59, s58, 31
	global_load_dword v178, v[2:3], off offset:512
	global_load_dword v176, v[2:3], off offset:768
	v_lshl_add_u64 v[2:3], s[18:19], 0, v[24:25]
	s_lshl_b64 s[18:19], s[58:59], 10
	s_add_u32 s18, s26, s18
	s_addc_u32 s19, s27, s19
	s_add_u32 s7, s18, 0x800
	s_addc_u32 s11, s19, 0
	global_load_dword v173, v[2:3], off
	global_load_dword v171, v[2:3], off offset:256
	v_lshl_add_u64 v[2:3], s[20:21], 0, v[24:25]
	s_and_b64 s[20:21], s[14:15], exec
	s_cselect_b32 s13, s18, s9
	s_cselect_b32 s20, s19, s28
	s_cmpk_lt_i32 s58, 0xfe
	s_cselect_b32 s21, s11, s20
	s_cselect_b32 s20, s7, s13
	s_or_b32 s56, s8, 20
	s_ashr_i32 s57, s56, 31
	global_load_dword v174, v[2:3], off offset:512
	global_load_dword v172, v[2:3], off offset:768
	v_lshl_add_u64 v[2:3], s[18:19], 0, v[24:25]
	s_lshl_b64 s[18:19], s[56:57], 10
	s_add_u32 s18, s26, s18
	s_addc_u32 s19, s27, s19
	s_add_u32 s7, s18, 0x800
	s_addc_u32 s11, s19, 0
	global_load_dword v169, v[2:3], off
	global_load_dword v167, v[2:3], off offset:256
	v_lshl_add_u64 v[2:3], s[20:21], 0, v[24:25]
	s_and_b64 s[20:21], s[14:15], exec
	s_cselect_b32 s13, s18, s16
	s_cselect_b32 s20, s19, s17
	s_cmpk_lt_i32 s56, 0xfe
	s_cselect_b32 s21, s11, s20
	s_cselect_b32 s20, s7, s13
	s_or_b32 s54, s8, 21
	s_ashr_i32 s55, s54, 31
	global_load_dword v170, v[2:3], off offset:512
	global_load_dword v168, v[2:3], off offset:768
	v_lshl_add_u64 v[2:3], s[18:19], 0, v[24:25]
	s_lshl_b64 s[18:19], s[54:55], 10
	s_add_u32 s18, s26, s18
	s_addc_u32 s19, s27, s19
	s_add_u32 s7, s18, 0x800
	s_addc_u32 s11, s19, 0
	global_load_dword v165, v[2:3], off
	global_load_dword v163, v[2:3], off offset:256
	v_lshl_add_u64 v[2:3], s[20:21], 0, v[24:25]
	s_and_b64 s[20:21], s[14:15], exec
	s_cselect_b32 s13, s18, s9
	s_cselect_b32 s20, s19, s28
	s_cmpk_lt_i32 s54, 0xfe
	s_cselect_b32 s21, s11, s20
	s_cselect_b32 s20, s7, s13
	s_or_b32 s52, s8, 22
	s_ashr_i32 s53, s52, 31
	global_load_dword v166, v[2:3], off offset:512
	global_load_dword v164, v[2:3], off offset:768
	v_lshl_add_u64 v[2:3], s[18:19], 0, v[24:25]
	s_lshl_b64 s[18:19], s[52:53], 10
	s_add_u32 s18, s26, s18
	s_addc_u32 s19, s27, s19
	s_add_u32 s7, s18, 0x800
	s_addc_u32 s11, s19, 0
	global_load_dword v161, v[2:3], off
	global_load_dword v159, v[2:3], off offset:256
	v_lshl_add_u64 v[2:3], s[20:21], 0, v[24:25]
	s_and_b64 s[20:21], s[14:15], exec
	s_cselect_b32 s13, s18, s16
	s_cselect_b32 s20, s19, s17
	s_cmpk_lt_i32 s52, 0xfe
	s_cselect_b32 s21, s11, s20
	s_cselect_b32 s20, s7, s13
	s_or_b32 s50, s8, 23
	s_ashr_i32 s51, s50, 31
	global_load_dword v162, v[2:3], off offset:512
	global_load_dword v160, v[2:3], off offset:768
	v_lshl_add_u64 v[2:3], s[18:19], 0, v[24:25]
	s_lshl_b64 s[18:19], s[50:51], 10
	s_add_u32 s18, s26, s18
	s_addc_u32 s19, s27, s19
	s_add_u32 s7, s18, 0x800
	s_addc_u32 s11, s19, 0
	global_load_dword v157, v[2:3], off
	global_load_dword v155, v[2:3], off offset:256
	v_lshl_add_u64 v[2:3], s[20:21], 0, v[24:25]
	s_and_b64 s[20:21], s[14:15], exec
	s_cselect_b32 s13, s18, s9
	s_cselect_b32 s20, s19, s28
	s_cmpk_lt_i32 s50, 0xfe
	s_cselect_b32 s21, s11, s20
	s_cselect_b32 s20, s7, s13
	s_or_b32 s48, s8, 24
	s_ashr_i32 s49, s48, 31
	global_load_dword v158, v[2:3], off offset:512
	global_load_dword v156, v[2:3], off offset:768
	v_lshl_add_u64 v[2:3], s[18:19], 0, v[24:25]
	s_lshl_b64 s[18:19], s[48:49], 10
	s_add_u32 s18, s26, s18
	s_addc_u32 s19, s27, s19
	s_add_u32 s7, s18, 0x800
	s_addc_u32 s11, s19, 0
	global_load_dword v153, v[2:3], off
	global_load_dword v151, v[2:3], off offset:256
	v_lshl_add_u64 v[2:3], s[20:21], 0, v[24:25]
	s_and_b64 s[20:21], s[14:15], exec
	s_cselect_b32 s13, s18, s16
	s_cselect_b32 s20, s19, s17
	s_cmpk_lt_i32 s48, 0xfe
	s_cselect_b32 s21, s11, s20
	s_cselect_b32 s20, s7, s13
	s_or_b32 s46, s8, 25
	s_ashr_i32 s47, s46, 31
	global_load_dword v154, v[2:3], off offset:512
	global_load_dword v152, v[2:3], off offset:768
	v_lshl_add_u64 v[2:3], s[18:19], 0, v[24:25]
	s_lshl_b64 s[18:19], s[46:47], 10
	s_add_u32 s18, s26, s18
	s_addc_u32 s19, s27, s19
	s_add_u32 s7, s18, 0x800
	s_addc_u32 s11, s19, 0
	global_load_dword v149, v[2:3], off
	global_load_dword v147, v[2:3], off offset:256
	v_lshl_add_u64 v[2:3], s[20:21], 0, v[24:25]
	s_and_b64 s[20:21], s[14:15], exec
	s_cselect_b32 s13, s18, s9
	s_cselect_b32 s20, s19, s28
	s_cmpk_lt_i32 s46, 0xfe
	s_cselect_b32 s21, s11, s20
	s_cselect_b32 s20, s7, s13
	s_or_b32 s44, s8, 26
	s_ashr_i32 s45, s44, 31
	global_load_dword v150, v[2:3], off offset:512
	global_load_dword v148, v[2:3], off offset:768
	v_lshl_add_u64 v[2:3], s[18:19], 0, v[24:25]
	s_lshl_b64 s[18:19], s[44:45], 10
	s_add_u32 s18, s26, s18
	s_addc_u32 s19, s27, s19
	s_add_u32 s7, s18, 0x800
	s_addc_u32 s11, s19, 0
	global_load_dword v145, v[2:3], off
	global_load_dword v143, v[2:3], off offset:256
	v_lshl_add_u64 v[2:3], s[20:21], 0, v[24:25]
	s_and_b64 s[20:21], s[14:15], exec
	s_cselect_b32 s13, s18, s16
	s_cselect_b32 s20, s19, s17
	s_cmpk_lt_i32 s44, 0xfe
	s_cselect_b32 s21, s11, s20
	s_cselect_b32 s20, s7, s13
	s_or_b32 s24, s8, 27
	s_ashr_i32 s25, s24, 31
	global_load_dword v146, v[2:3], off offset:512
	global_load_dword v144, v[2:3], off offset:768
	v_lshl_add_u64 v[2:3], s[18:19], 0, v[24:25]
	s_lshl_b64 s[18:19], s[24:25], 10
	s_add_u32 s18, s26, s18
	s_addc_u32 s19, s27, s19
	s_add_u32 s7, s18, 0x800
	s_addc_u32 s11, s19, 0
	global_load_dword v141, v[2:3], off
	global_load_dword v139, v[2:3], off offset:256
	v_lshl_add_u64 v[2:3], s[20:21], 0, v[24:25]
	s_and_b64 s[20:21], s[14:15], exec
	s_cselect_b32 s13, s18, s9
	s_cselect_b32 s20, s19, s28
	s_cmpk_lt_i32 s24, 0xfe
	s_cselect_b32 s21, s11, s20
	s_cselect_b32 s20, s7, s13
	s_or_b32 s22, s8, 28
	s_ashr_i32 s23, s22, 31
	global_load_dword v142, v[2:3], off offset:512
	global_load_dword v140, v[2:3], off offset:768
	v_lshl_add_u64 v[2:3], s[18:19], 0, v[24:25]
	s_lshl_b64 s[18:19], s[22:23], 10
	s_add_u32 s18, s26, s18
	s_addc_u32 s19, s27, s19
	s_add_u32 s7, s18, 0x800
	s_addc_u32 s11, s19, 0
	global_load_dword v137, v[2:3], off
	global_load_dword v135, v[2:3], off offset:256
	v_lshl_add_u64 v[2:3], s[20:21], 0, v[24:25]
	s_and_b64 s[20:21], s[14:15], exec
	s_cselect_b32 s13, s18, s16
	s_cselect_b32 s20, s19, s17
	s_cmpk_lt_i32 s22, 0xfe
	global_load_dword v138, v[2:3], off offset:512
	global_load_dword v136, v[2:3], off offset:768
	s_cselect_b32 s21, s11, s20
	s_cselect_b32 s20, s7, s13
	v_lshl_add_u64 v[2:3], s[18:19], 0, v[24:25]
	global_load_dword v129, v[2:3], off
	global_load_dword v127, v[2:3], off offset:256
	v_lshl_add_u64 v[2:3], s[20:21], 0, v[24:25]
	s_or_b32 s20, s8, 29
	s_ashr_i32 s21, s20, 31
	s_lshl_b64 s[18:19], s[20:21], 10
	s_add_u32 s18, s26, s18
	s_addc_u32 s19, s27, s19
	s_add_u32 s7, s18, 0x800
	s_addc_u32 s11, s19, 0
	s_and_b64 s[30:31], s[14:15], exec
	s_cselect_b32 s13, s18, s9
	s_cselect_b32 s21, s19, s28
	s_cmpk_lt_i32 s20, 0xfe
	global_load_dword v134, v[2:3], off offset:512
	global_load_dword v128, v[2:3], off offset:768
	s_cselect_b32 s31, s11, s21
	s_cselect_b32 s30, s7, s13
	v_lshl_add_u64 v[2:3], s[18:19], 0, v[24:25]
	s_or_b32 s18, s8, 30
	s_ashr_i32 s19, s18, 31
	global_load_dword v125, v[2:3], off
	global_load_dword v123, v[2:3], off offset:256
	v_lshl_add_u64 v[2:3], s[30:31], 0, v[24:25]
	s_lshl_b64 s[30:31], s[18:19], 10
	s_add_u32 s30, s26, s30
	s_addc_u32 s31, s27, s31
	s_add_u32 s7, s30, 0x800
	s_addc_u32 s11, s31, 0
	s_and_b64 s[34:35], s[14:15], exec
	s_cselect_b32 s13, s30, s16
	s_cselect_b32 s16, s31, s17
	s_cmpk_lt_i32 s18, 0xfe
	global_load_dword v126, v[2:3], off offset:512
	global_load_dword v124, v[2:3], off offset:768
	s_cselect_b32 s17, s11, s16
	s_cselect_b32 s16, s7, s13
	v_lshl_add_u64 v[2:3], s[30:31], 0, v[24:25]
	global_load_dword v121, v[2:3], off
	global_load_dword v119, v[2:3], off offset:256
	v_lshl_add_u64 v[2:3], s[16:17], 0, v[24:25]
	s_or_b32 s16, s8, 31
	s_ashr_i32 s17, s16, 31
	s_lshl_b64 s[30:31], s[16:17], 10
	s_add_u32 s26, s26, s30
	s_addc_u32 s27, s27, s31
	s_add_u32 s7, s26, 0x800
	s_addc_u32 s11, s27, 0
	s_and_b64 s[14:15], s[14:15], exec
	s_cselect_b32 s9, s26, s9
	s_cselect_b32 s13, s27, s28
	s_cmpk_lt_i32 s16, 0xfe
	global_load_dword v122, v[2:3], off offset:512
	global_load_dword v120, v[2:3], off offset:768
	s_cselect_b32 s15, s11, s13
	s_cselect_b32 s14, s7, s9
	v_lshl_add_u64 v[2:3], s[26:27], 0, v[24:25]
	global_load_dword v117, v[2:3], off
	global_load_dword v115, v[2:3], off offset:256
	v_lshl_add_u64 v[2:3], s[14:15], 0, v[24:25]
	global_load_dword v118, v[2:3], off offset:512
	global_load_dword v116, v[2:3], off offset:768
	s_movk_i32 s7, 0x2000
	s_mov_b64 s[14:15], 0x800
	v_cmp_gt_i32_e32 vcc, s7, v130
	v_lshl_add_u32 v4, v130, 2, s96
	s_waitcnt vmcnt(0) lgkmcnt(0)
	s_barrier
	s_and_saveexec_b64 s[68:69], vcc
	s_cbranch_execz .LBB0_1715
	s_lshl_b32 s7, s5, 15
	v_mov_b32_e32 v2, s7
	v_mov_b32_e32 v3, v133
	v_ashrrev_i32_e32 v131, 31, v130
	v_add_u32_e32 v5, 0xfffffe00, v130
	v_lshl_add_u64 v[2:3], v[130:131], 2, v[2:3]
	s_mov_b64 s[72:73], 0
	s_movk_i32 s7, 0x1dff
	v_mov_b32_e32 v6, v4
.LBB0_1714:
	v_mov_b64_e32 v[8:9], s[0:1]
	global_load_dwordx2 v[8:9], v[8:9], off offset:144 sc0 sc1
	s_waitcnt vmcnt(0)
	v_add_u32_e32 v5, 0x200, v5
	v_cmp_lt_i32_e32 vcc, s7, v5
	s_or_b64 s[72:73], vcc, s[72:73]
	s_waitcnt lgkmcnt(0)
	v_lshl_add_u64 v[8:9], v[8:9], 0, v[2:3]
	global_load_dword v7, v[8:9], off
	v_lshl_add_u64 v[2:3], v[2:3], 0, s[14:15]
	s_waitcnt vmcnt(0)
	ds_write_b32 v6, v7
	v_add_u32_e32 v6, 0x800, v6
	s_andn2_b64 exec, exec, s[72:73]
	s_cbranch_execnz .LBB0_1714
.LBB0_1715:
	s_or_b64 exec, exec, s[68:69]
	s_movk_i32 s7, 0x7f
	v_cmp_lt_i32_e32 vcc, s7, v130
	s_and_saveexec_b64 s[14:15], vcc
	s_xor_b64 s[14:15], exec, s[14:15]
	s_lshl_b32 s7, s5, 7
	s_or_saveexec_b64 s[14:15], s[14:15]
	v_mov_b32_e32 v58, s7
	s_xor_b64 exec, exec, s[14:15]
	s_cbranch_execz .LBB0_1721
	v_mov_b64_e32 v[2:3], s[0:1]
	global_load_dwordx2 v[6:7], v[2:3], off offset:136 sc0 sc1
	s_waitcnt vmcnt(0)
	s_lshl_b32 s7, s5, 7
	v_add_u32_e32 v2, s7, v130
	v_ashrrev_i32_e32 v3, 31, v2
	s_add_u32 s68, s38, 0x6200000
	s_addc_u32 s69, s39, 0
	s_mov_b32 s9, 0
	s_waitcnt lgkmcnt(0)
	v_lshl_add_u64 v[6:7], v[2:3], 2, v[6:7]
	global_load_dword v3, v[6:7], off
.LBB0_1719:
	v_add_u32_e32 v6, s9, v2
	v_add_u32_e32 v8, 0x200, v6
	v_add_u32_e32 v10, 0x400, v6
	v_add_u32_e32 v12, 0x600, v6
	v_ashrrev_i32_e32 v7, 31, v6
	v_add_u32_e32 v14, 0x800, v6
	v_add_u32_e32 v16, 0xa00, v6
	v_add_u32_e32 v18, 0xc00, v6
	v_add_u32_e32 v26, 0xe00, v6
	v_ashrrev_i32_e32 v9, 31, v8
	v_ashrrev_i32_e32 v11, 31, v10
	v_ashrrev_i32_e32 v13, 31, v12
	v_lshl_add_u64 v[6:7], v[6:7], 2, s[68:69]
	v_ashrrev_i32_e32 v15, 31, v14
	v_ashrrev_i32_e32 v17, 31, v16
	v_ashrrev_i32_e32 v19, 31, v18
	v_ashrrev_i32_e32 v27, 31, v26
	v_lshl_add_u64 v[8:9], v[8:9], 2, s[68:69]
	v_lshl_add_u64 v[10:11], v[10:11], 2, s[68:69]
	v_lshl_add_u64 v[12:13], v[12:13], 2, s[68:69]
	v_lshl_add_u64 v[14:15], v[14:15], 2, s[68:69]
	v_lshl_add_u64 v[16:17], v[16:17], 2, s[68:69]
	v_lshl_add_u64 v[18:19], v[18:19], 2, s[68:69]
	v_lshl_add_u64 v[26:27], v[26:27], 2, s[68:69]
	global_load_dword v5, v[6:7], off
	s_nop 0
	global_load_dword v6, v[8:9], off
	global_load_dword v7, v[10:11], off
	s_nop 0
	global_load_dword v8, v[12:13], off
	global_load_dword v9, v[14:15], off
	global_load_dword v10, v[16:17], off
	global_load_dword v11, v[18:19], off
	s_nop 0
	global_load_dword v12, v[26:27], off
	s_addk_i32 s9, 0x1000
	s_cmpk_eq_i32 s9, 0x4000
	s_waitcnt vmcnt(0) lgkmcnt(0)
	v_add_f32_e32 v3, v3, v5
	v_add_f32_e32 v3, v3, v6
	v_add_f32_e32 v3, v3, v7
	v_add_f32_e32 v3, v3, v8
	v_add_f32_e32 v3, v3, v9
	v_add_f32_e32 v3, v3, v10
	v_add_f32_e32 v3, v3, v11
	v_add_f32_e32 v3, v3, v12
	s_cbranch_scc0 .LBB0_1719
	v_mov_b32_e32 v58, s7
	ds_write_b32 v4, v3 offset:32768

.LBB0_1784:
	v_add_u32_e32 v32, s6, v114
	ds_read2_b32 v[28:29], v27 offset1:16
	ds_read2_b32 v[30:31], v32 offset1:4
	v_add_u32_e32 v33, 0x800, v27
	s_add_i32 s6, s6, 64
	s_cmpk_eq_i32 s6, 0x200
	s_waitcnt lgkmcnt(0)
	v_mfma_f32_16x16x4_f32 v[14:17], v30, v28, v[14:17]
	v_mfma_f32_16x16x4_f32 v[10:13], v30, v29, v[10:13]
	ds_read2_b32 v[28:29], v27 offset0:32 offset1:48
	s_waitcnt lgkmcnt(0)
	v_mfma_f32_16x16x4_f32 v[6:9], v30, v28, v[6:9]
	v_mfma_f32_16x16x4_f32 v[2:5], v30, v29, v[2:5]
	v_add_u32_e32 v30, 0x400, v27
	ds_read2_b32 v[28:29], v30 offset1:16
	s_waitcnt lgkmcnt(0)
	v_mfma_f32_16x16x4_f32 v[14:17], v31, v28, v[14:17]
	v_mfma_f32_16x16x4_f32 v[10:13], v31, v29, v[10:13]
	ds_read2_b32 v[28:29], v30 offset0:32 offset1:48
	s_waitcnt lgkmcnt(0)
	v_mfma_f32_16x16x4_f32 v[6:9], v31, v28, v[6:9]
	v_mfma_f32_16x16x4_f32 v[2:5], v31, v29, v[2:5]
	ds_read2_b32 v[28:29], v32 offset0:8 offset1:12
	ds_read2_b32 v[30:31], v33 offset1:16
	s_waitcnt lgkmcnt(0)
	v_mfma_f32_16x16x4_f32 v[14:17], v28, v30, v[14:17]
	v_mfma_f32_16x16x4_f32 v[10:13], v28, v31, v[10:13]
	ds_read2_b32 v[30:31], v33 offset0:32 offset1:48
	s_waitcnt lgkmcnt(0)
	v_mfma_f32_16x16x4_f32 v[6:9], v28, v30, v[6:9]
	v_mfma_f32_16x16x4_f32 v[2:5], v28, v31, v[2:5]
	v_add_u32_e32 v28, 0xc00, v27
	ds_read2_b32 v[30:31], v28 offset1:16
	v_add_u32_e32 v27, 0x1000, v27
	s_waitcnt lgkmcnt(0)
	v_mfma_f32_16x16x4_f32 v[14:17], v29, v30, v[14:17]
	v_mfma_f32_16x16x4_f32 v[10:13], v29, v31, v[10:13]
	ds_read2_b32 v[30:31], v28 offset0:32 offset1:48
	s_waitcnt lgkmcnt(0)
	v_mfma_f32_16x16x4_f32 v[6:9], v29, v30, v[6:9]
	v_mfma_f32_16x16x4_f32 v[2:5], v29, v31, v[2:5]
	s_cbranch_scc0 .LBB0_1784
	s_ashr_i32 s6, s40, 3
	s_lshl_b32 s9, s5, 1
	s_lshl_b32 s28, s17, 7
	s_ashr_i32 s7, s6, 31
	s_add_u32 s6, s9, s6
	s_addc_u32 s7, 0, s7
	v_add_u32_e32 v131, s8, v112
	s_lshl_b64 s[66:67], s[6:7], 17
	s_movk_i32 s6, 0xfd
	v_cmp_lt_i32_e32 vcc, s6, v131
	s_and_b64 s[70:71], s[14:15], vcc
	s_add_u32 s26, s38, 0x28800000
	s_addc_u32 s27, s39, 0
	v_ashrrev_i32_e32 v34, 1, v131
	s_add_u32 s64, s26, s66
	v_add_u32_e32 v32, s28, v34
	s_addc_u32 s65, s27, s67
	s_waitcnt lgkmcnt(0)
	v_add3_u32 v28, s13, -8, v58
	v_mov_b32_e32 v29, 0
	v_ashrrev_i32_e32 v33, 31, v32
	s_add_u32 s10, s38, 0x6600000
	v_lshlrev_b64 v[30:31], 16, v[28:29]
	v_lshlrev_b64 v[32:33], 8, v[32:33]
	s_addc_u32 s11, s39, 0
	v_ashrrev_i32_e32 v35, 31, v34
	s_mov_b64 s[6:7], -1
	v_lshl_add_u64 v[42:43], s[64:65], 0, v[32:33]
	v_lshl_add_u64 v[40:41], s[10:11], 0, v[30:31]
	v_lshlrev_b64 v[34:35], 9, v[34:35]
	s_and_b64 vcc, exec, s[72:73]
	v_lshlrev_b32_e32 v28, 1, v111
	s_cbranch_vccz .LBB0_1787
	v_cndmask_b32_e64 v27, v14, 0, s[70:71]
	v_bfe_u32 v44, v27, 16, 1
	s_movk_i32 s6, 0x7fff
	v_add3_u32 v27, v27, v44, s6
	v_lshl_add_u64 v[44:45], v[42:43], 0, v[28:29]
	s_mov_b64 s[6:7], 0
	global_store_short_d16_hi v[44:45], v27, off
.LBB0_1787:
	s_xor_b64 s[74:75], s[70:71], -1
	s_andn2_b64 vcc, exec, s[6:7]
	v_lshl_add_u64 v[44:45], v[40:41], 0, v[34:35]
	s_cbranch_vccnz .LBB0_1791
	s_and_saveexec_b64 s[6:7], s[74:75]
	s_cbranch_execz .LBB0_1790
	v_mov_b32_e32 v27, 0
	v_lshl_add_u64 v[46:47], v[44:45], 0, v[26:27]
	global_store_dword v[46:47], v14, off

.LBB0_1791:
	v_cndmask_b32_e64 v14, 0, 1, s[72:73]
	v_cmp_ne_u32_e64 s[6:7], 1, v14
	s_andn2_b64 vcc, exec, s[72:73]
	s_mov_b64 s[72:73], -1
	s_cbranch_vccnz .LBB0_1797
	v_cndmask_b32_e64 v14, v10, 0, s[70:71]
	v_bfe_u32 v27, v14, 16, 1
	s_movk_i32 s13, 0x7fff
	v_mov_b32_e32 v29, 0
	v_add3_u32 v14, v14, v27, s13
	v_lshl_add_u64 v[46:47], v[42:43], 0, v[28:29]
	global_store_short_d16_hi v[46:47], v14, off offset:32
	s_cbranch_execz .LBB0_1798

.LBB0_1794:
	v_cndmask_b32_e64 v10, v6, 0, s[70:71]
	v_bfe_u32 v14, v10, 16, 1
	s_movk_i32 s13, 0x7fff
	v_mov_b32_e32 v29, 0
	v_add3_u32 v10, v10, v14, s13
	v_lshl_add_u64 v[46:47], v[42:43], 0, v[28:29]
	global_store_short_d16_hi v[46:47], v10, off offset:64
	s_cbranch_execz .LBB0_1802

.LBB0_1796:
	v_cndmask_b32_e64 v6, v2, 0, s[70:71]
	v_bfe_u32 v10, v6, 16, 1
	s_movk_i32 s13, 0x7fff
	v_mov_b32_e32 v29, 0
	v_add3_u32 v6, v6, v10, s13
	v_lshl_add_u64 v[42:43], v[42:43], 0, v[28:29]
	global_store_short_d16_hi v[42:43], v6, off offset:96
	s_cbranch_execnz .LBB0_1809
	s_branch .LBB0_1806

.LBB0_1798:
	s_and_saveexec_b64 s[72:73], s[74:75]
	s_cbranch_execz .LBB0_1800
	v_mov_b32_e32 v27, 0
	v_lshl_add_u64 v[46:47], v[44:45], 0, v[26:27]
	global_store_dword v[46:47], v10, off offset:64

.LBB0_1802:
	s_and_saveexec_b64 s[72:73], s[74:75]
	s_cbranch_execz .LBB0_1804
	v_mov_b32_e32 v27, 0
	v_lshl_add_u64 v[46:47], v[44:45], 0, v[26:27]
	global_store_dword v[46:47], v6, off offset:128

.LBB0_1806:
	s_and_saveexec_b64 s[70:71], s[74:75]
	s_cbranch_execz .LBB0_1808
	v_mov_b32_e32 v27, 0
	v_lshl_add_u64 v[42:43], v[44:45], 0, v[26:27]
	global_store_dword v[42:43], v2, off offset:192

.LBB0_1809:
	s_movk_i32 s13, 0xfc
	v_cmp_lt_i32_e32 vcc, s13, v131
	s_and_b64 s[70:71], s[14:15], vcc
	s_add_u32 s66, s38, s66
	s_addc_u32 s67, s39, s67
	v_lshl_add_u64 v[32:33], s[66:67], 0, v[32:33]
	s_mov_b64 s[30:31], 0x28800080
	v_lshl_add_u64 v[42:43], s[38:39], 0, v[30:31]
	s_mov_b64 s[74:75], -1
	v_lshl_add_u64 v[44:45], v[32:33], 0, s[30:31]
	v_lshl_add_u64 v[30:31], v[42:43], 0, v[34:35]
	s_and_b64 vcc, exec, s[6:7]
	s_mov_b64 s[76:77], 0x6600100
	s_cbranch_vccnz .LBB0_1811
	v_cndmask_b32_e64 v2, v15, 0, s[70:71]
	v_bfe_u32 v6, v2, 16, 1
	s_movk_i32 s13, 0x7fff
	v_mov_b32_e32 v29, 0
	v_add3_u32 v2, v2, v6, s13
	v_lshl_add_u64 v[32:33], v[44:45], 0, v[28:29]
	s_mov_b64 s[74:75], 0
	global_store_short_d16_hi v[32:33], v2, off
.LBB0_1811:
	s_xor_b64 s[72:73], s[70:71], -1
	s_andn2_b64 vcc, exec, s[74:75]
	v_lshl_add_u64 v[46:47], v[30:31], 0, s[76:77]
	s_cbranch_vccnz .LBB0_1815
	s_and_saveexec_b64 s[74:75], s[72:73]
	s_cbranch_execz .LBB0_1814
	v_mov_b32_e32 v27, 0
	v_lshl_add_u64 v[30:31], v[46:47], 0, v[26:27]
	global_store_dword v[30:31], v15, off

.LBB0_1815:
	v_or_b32_e32 v109, 16, v111
	s_mov_b64 s[74:75], -1
	s_and_b64 vcc, exec, s[6:7]
	v_lshlrev_b32_e32 v30, 1, v109
	s_cbranch_vccnz .LBB0_1817
	v_cndmask_b32_e64 v2, v11, 0, s[70:71]
	v_bfe_u32 v6, v2, 16, 1
	s_movk_i32 s13, 0x7fff
	v_mov_b32_e32 v31, 0
	v_add3_u32 v2, v2, v6, s13
	v_lshl_add_u64 v[14:15], v[44:45], 0, v[30:31]
	s_mov_b64 s[74:75], 0
	global_store_short_d16_hi v[14:15], v2, off
.LBB0_1817:
	s_andn2_b64 vcc, exec, s[74:75]
	s_cbranch_vccnz .LBB0_1821
	s_and_saveexec_b64 s[74:75], s[72:73]
	s_cbranch_execz .LBB0_1820
	v_lshlrev_b32_e32 v14, 2, v109
	v_mov_b32_e32 v15, 0
	v_lshl_add_u64 v[14:15], v[46:47], 0, v[14:15]
	global_store_dword v[14:15], v11, off

.LBB0_1821:
	v_or_b32_e32 v110, 32, v111
	s_mov_b64 s[74:75], -1
	s_and_b64 vcc, exec, s[6:7]
	v_lshlrev_b32_e32 v32, 1, v110
	s_cbranch_vccnz .LBB0_1823
	v_cndmask_b32_e64 v2, v7, 0, s[70:71]
	v_bfe_u32 v6, v2, 16, 1
	s_movk_i32 s13, 0x7fff
	v_mov_b32_e32 v33, 0
	v_add3_u32 v2, v2, v6, s13
	v_lshl_add_u64 v[10:11], v[44:45], 0, v[32:33]
	s_mov_b64 s[74:75], 0
	global_store_short_d16_hi v[10:11], v2, off
.LBB0_1823:
	s_andn2_b64 vcc, exec, s[74:75]
	s_cbranch_vccnz .LBB0_1827
	s_and_saveexec_b64 s[74:75], s[72:73]
	s_cbranch_execz .LBB0_1826
	v_lshlrev_b32_e32 v10, 2, v110
	v_mov_b32_e32 v11, 0
	v_lshl_add_u64 v[10:11], v[46:47], 0, v[10:11]
	global_store_dword v[10:11], v7, off

.LBB0_1827:
	v_or_b32_e32 v111, 48, v111
	s_mov_b64 s[74:75], -1
	s_and_b64 vcc, exec, s[6:7]
	v_lshlrev_b32_e32 v34, 1, v111
	s_cbranch_vccnz .LBB0_1829
	v_cndmask_b32_e64 v2, v3, 0, s[70:71]
	v_bfe_u32 v6, v2, 16, 1
	s_movk_i32 s13, 0x7fff
	v_mov_b32_e32 v35, 0
	v_add3_u32 v2, v2, v6, s13
	v_lshl_add_u64 v[6:7], v[44:45], 0, v[34:35]
	s_mov_b64 s[74:75], 0
	global_store_short_d16_hi v[6:7], v2, off
.LBB0_1829:
	s_andn2_b64 vcc, exec, s[74:75]
	s_cbranch_vccnz .LBB0_1833
	s_and_saveexec_b64 s[70:71], s[72:73]
	s_cbranch_execz .LBB0_1832
	v_lshlrev_b32_e32 v6, 2, v111
	v_mov_b32_e32 v7, 0
	v_lshl_add_u64 v[6:7], v[46:47], 0, v[6:7]
	global_store_dword v[6:7], v3, off

.LBB0_1833:
	v_or_b32_e32 v2, 2, v131
	v_ashrrev_i32_e32 v6, 1, v2
	s_movk_i32 s13, 0xfd
	v_cmp_lt_i32_e32 vcc, s13, v2
	v_add_u32_e32 v2, s28, v6
	v_ashrrev_i32_e32 v3, 31, v2
	v_lshlrev_b64 v[2:3], 8, v[2:3]
	v_ashrrev_i32_e32 v7, 31, v6
	s_and_b64 s[70:71], s[14:15], vcc
	s_mov_b64 s[74:75], -1
	v_lshl_add_u64 v[2:3], s[64:65], 0, v[2:3]
	s_and_b64 vcc, exec, s[6:7]
	v_lshlrev_b64 v[6:7], 9, v[6:7]
	s_cbranch_vccnz .LBB0_1841
	v_cndmask_b32_e64 v10, v16, 0, s[70:71]
	v_bfe_u32 v11, v10, 16, 1
	s_movk_i32 s13, 0x7fff
	v_mov_b32_e32 v29, 0
	v_add3_u32 v14, v10, v11, s13
	v_lshl_add_u64 v[10:11], v[2:3], 0, v[28:29]
	global_store_short_d16_hi v[10:11], v14, off
	s_xor_b64 s[72:73], s[70:71], -1
	v_lshl_add_u64 v[6:7], v[40:41], 0, v[6:7]
	s_cbranch_execz .LBB0_1842

.LBB0_1836:
	v_cndmask_b32_e64 v10, v12, 0, s[70:71]
	v_bfe_u32 v11, v10, 16, 1
	s_movk_i32 s13, 0x7fff
	v_mov_b32_e32 v29, 0
	v_add3_u32 v14, v10, v11, s13
	v_lshl_add_u64 v[10:11], v[2:3], 0, v[28:29]
	global_store_short_d16_hi v[10:11], v14, off offset:32
	s_cbranch_execz .LBB0_1846

.LBB0_1838:
	v_cndmask_b32_e64 v10, v8, 0, s[70:71]
	v_bfe_u32 v11, v10, 16, 1
	s_movk_i32 s13, 0x7fff
	v_mov_b32_e32 v29, 0
	v_add3_u32 v12, v10, v11, s13
	v_lshl_add_u64 v[10:11], v[2:3], 0, v[28:29]
	global_store_short_d16_hi v[10:11], v12, off offset:64
	s_cbranch_execz .LBB0_1850

.LBB0_1840:
	v_cndmask_b32_e64 v8, v4, 0, s[70:71]
	v_bfe_u32 v10, v8, 16, 1
	s_movk_i32 s13, 0x7fff
	v_mov_b32_e32 v29, 0
	v_add3_u32 v8, v8, v10, s13
	v_lshl_add_u64 v[2:3], v[2:3], 0, v[28:29]
	global_store_short_d16_hi v[2:3], v8, off offset:96
	s_cbranch_execnz .LBB0_1857
	s_branch .LBB0_1854

.LBB0_1842:
	s_and_saveexec_b64 s[74:75], s[72:73]
	s_cbranch_execz .LBB0_1844
	v_mov_b32_e32 v27, 0
	v_lshl_add_u64 v[10:11], v[6:7], 0, v[26:27]
	global_store_dword v[10:11], v16, off

.LBB0_1846:
	s_and_saveexec_b64 s[74:75], s[72:73]
	s_cbranch_execz .LBB0_1848
	v_mov_b32_e32 v27, 0
	v_lshl_add_u64 v[10:11], v[6:7], 0, v[26:27]
	global_store_dword v[10:11], v12, off offset:64

.LBB0_1850:
	s_and_saveexec_b64 s[74:75], s[72:73]
	s_cbranch_execz .LBB0_1852
	v_mov_b32_e32 v27, 0
	v_lshl_add_u64 v[10:11], v[6:7], 0, v[26:27]
	global_store_dword v[10:11], v8, off offset:128

.LBB0_1854:
	s_and_saveexec_b64 s[70:71], s[72:73]
	s_cbranch_execz .LBB0_1856
	v_mov_b32_e32 v27, 0
	v_lshl_add_u64 v[2:3], v[6:7], 0, v[26:27]
	global_store_dword v[2:3], v4, off offset:192

.LBB0_1857:
	v_or_b32_e32 v2, 3, v131
	v_ashrrev_i32_e32 v6, 1, v2
	s_movk_i32 s13, 0xfd
	v_cmp_lt_i32_e32 vcc, s13, v2
	v_add_u32_e32 v2, s28, v6
	v_ashrrev_i32_e32 v3, 31, v2
	v_lshlrev_b64 v[2:3], 8, v[2:3]
	v_ashrrev_i32_e32 v7, 31, v6
	v_lshl_add_u64 v[2:3], s[66:67], 0, v[2:3]
	v_lshlrev_b64 v[6:7], 9, v[6:7]
	s_and_b64 s[70:71], s[14:15], vcc
	s_mov_b64 s[74:75], -1
	v_lshl_add_u64 v[2:3], v[2:3], 0, s[30:31]
	v_lshl_add_u64 v[6:7], v[42:43], 0, v[6:7]
	s_and_b64 vcc, exec, s[6:7]
	s_cbranch_vccnz .LBB0_1865
	v_cndmask_b32_e64 v4, v17, 0, s[70:71]
	v_bfe_u32 v8, v4, 16, 1
	s_movk_i32 s13, 0x7fff
	v_mov_b32_e32 v29, 0
	v_add3_u32 v4, v4, v8, s13
	v_lshl_add_u64 v[10:11], v[2:3], 0, v[28:29]
	global_store_short_d16_hi v[10:11], v4, off
	s_xor_b64 s[72:73], s[70:71], -1
	v_lshl_add_u64 v[6:7], v[6:7], 0, s[76:77]
	s_cbranch_execz .LBB0_1866

.LBB0_1860:
	v_cndmask_b32_e64 v4, v13, 0, s[70:71]
	v_bfe_u32 v8, v4, 16, 1
	s_movk_i32 s13, 0x7fff
	v_mov_b32_e32 v31, 0
	v_add3_u32 v4, v4, v8, s13
	v_lshl_add_u64 v[10:11], v[2:3], 0, v[30:31]
	global_store_short_d16_hi v[10:11], v4, off
	s_cbranch_execz .LBB0_1870

.LBB0_1862:
	v_cndmask_b32_e64 v4, v9, 0, s[70:71]
	v_bfe_u32 v8, v4, 16, 1
	s_movk_i32 s13, 0x7fff
	v_mov_b32_e32 v33, 0
	v_add3_u32 v4, v4, v8, s13
	v_lshl_add_u64 v[10:11], v[2:3], 0, v[32:33]
	global_store_short_d16_hi v[10:11], v4, off
	s_cbranch_execz .LBB0_1874

.LBB0_1864:
	v_cndmask_b32_e64 v4, v5, 0, s[70:71]
	v_bfe_u32 v8, v4, 16, 1
	s_movk_i32 s13, 0x7fff
	v_mov_b32_e32 v35, 0
	v_add3_u32 v4, v4, v8, s13
	v_lshl_add_u64 v[2:3], v[2:3], 0, v[34:35]
	global_store_short_d16_hi v[2:3], v4, off
	s_cbranch_execnz .LBB0_1881
	s_branch .LBB0_1878

.LBB0_1866:
	s_and_saveexec_b64 s[74:75], s[72:73]
	s_cbranch_execz .LBB0_1868
	v_mov_b32_e32 v27, 0
	v_lshl_add_u64 v[10:11], v[6:7], 0, v[26:27]
	global_store_dword v[10:11], v17, off

.LBB0_1870:
	s_and_saveexec_b64 s[74:75], s[72:73]
	s_cbranch_execz .LBB0_1872
	v_lshlrev_b32_e32 v10, 2, v109
	v_mov_b32_e32 v11, 0
	v_lshl_add_u64 v[10:11], v[6:7], 0, v[10:11]
	global_store_dword v[10:11], v13, off

.LBB0_1874:
	s_and_saveexec_b64 s[74:75], s[72:73]
	s_cbranch_execz .LBB0_1876
	v_lshlrev_b32_e32 v10, 2, v110
	v_mov_b32_e32 v11, 0
	v_lshl_add_u64 v[10:11], v[6:7], 0, v[10:11]
	global_store_dword v[10:11], v9, off

.LBB0_1878:
	s_and_saveexec_b64 s[70:71], s[72:73]
	s_cbranch_execz .LBB0_1880
	v_lshlrev_b32_e32 v2, 2, v111
	v_mov_b32_e32 v3, 0
	v_lshl_add_u64 v[2:3], v[6:7], 0, v[2:3]
	global_store_dword v[2:3], v5, off

.LBB0_1944:
	v_add_u32_e32 v29, s13, v114
	ds_read2_b32 v[36:37], v27 offset1:16
	ds_read2_b32 v[38:39], v29 offset1:4
	v_add_u32_e32 v31, 0x400, v27
	s_add_i32 s13, s13, 64
	s_cmpk_lg_i32 s13, 0x200
	s_waitcnt lgkmcnt(0)
	v_mfma_f32_16x16x4_f32 v[14:17], v38, v36, v[14:17]
	v_mfma_f32_16x16x4_f32 v[10:13], v38, v37, v[10:13]
	ds_read2_b32 v[36:37], v27 offset0:32 offset1:48
	s_waitcnt lgkmcnt(0)
	v_mfma_f32_16x16x4_f32 v[6:9], v38, v36, v[6:9]
	v_mfma_f32_16x16x4_f32 v[2:5], v38, v37, v[2:5]
	ds_read2_b32 v[36:37], v31 offset1:16
	s_waitcnt lgkmcnt(0)
	v_mfma_f32_16x16x4_f32 v[14:17], v39, v36, v[14:17]
	v_mfma_f32_16x16x4_f32 v[10:13], v39, v37, v[10:13]
	ds_read2_b32 v[36:37], v31 offset0:32 offset1:48
	v_add_u32_e32 v31, 0x800, v27
	s_waitcnt lgkmcnt(0)
	v_mfma_f32_16x16x4_f32 v[6:9], v39, v36, v[6:9]
	v_mfma_f32_16x16x4_f32 v[2:5], v39, v37, v[2:5]
	ds_read2_b32 v[36:37], v29 offset0:8 offset1:12
	ds_read2_b32 v[38:39], v31 offset1:16
	v_add_u32_e32 v29, 0xc00, v27
	v_add_u32_e32 v27, 0x1000, v27
	s_waitcnt lgkmcnt(0)
	v_mfma_f32_16x16x4_f32 v[14:17], v36, v38, v[14:17]
	v_mfma_f32_16x16x4_f32 v[10:13], v36, v39, v[10:13]
	ds_read2_b32 v[38:39], v31 offset0:32 offset1:48
	s_waitcnt lgkmcnt(0)
	v_mfma_f32_16x16x4_f32 v[6:9], v36, v38, v[6:9]
	v_mfma_f32_16x16x4_f32 v[2:5], v36, v39, v[2:5]
	ds_read2_b32 v[38:39], v29 offset1:16
	s_waitcnt lgkmcnt(0)
	v_mfma_f32_16x16x4_f32 v[14:17], v37, v38, v[14:17]
	v_mfma_f32_16x16x4_f32 v[10:13], v37, v39, v[10:13]
	ds_read2_b32 v[38:39], v29 offset0:32 offset1:48
	s_waitcnt lgkmcnt(0)
	v_mfma_f32_16x16x4_f32 v[6:9], v37, v38, v[6:9]
	v_mfma_f32_16x16x4_f32 v[2:5], v37, v39, v[2:5]
	s_cbranch_scc1 .LBB0_1944
	v_add_u32_e32 v115, s12, v112
	v_ashrrev_i32_e32 v38, 1, v115
	v_add_u32_e32 v36, s28, v38
	s_waitcnt lgkmcnt(0)
	s_movk_i32 s12, 0xfd
	v_ashrrev_i32_e32 v37, 31, v36
	v_cmp_lt_i32_e32 vcc, s12, v115
	v_lshlrev_b64 v[36:37], 8, v[36:37]
	v_ashrrev_i32_e32 v39, 31, v38
	s_and_b64 s[12:13], s[14:15], vcc
	s_mov_b64 s[18:19], -1
	v_lshl_add_u64 v[44:45], s[64:65], 0, v[36:37]
	s_and_b64 vcc, exec, s[6:7]
	v_lshlrev_b64 v[38:39], 9, v[38:39]
	s_cbranch_vccnz .LBB0_1953
	v_cndmask_b32_e64 v27, v14, 0, s[12:13]
	v_bfe_u32 v29, v27, 16, 1
	s_movk_i32 s16, 0x7fff
	v_add3_u32 v27, v27, v29, s16
	v_mov_b32_e32 v29, 0
	v_lshl_add_u64 v[46:47], v[44:45], 0, v[28:29]
	global_store_short_d16_hi v[46:47], v27, off
	s_xor_b64 s[16:17], s[12:13], -1
	v_lshl_add_u64 v[46:47], v[40:41], 0, v[38:39]
	s_cbranch_execz .LBB0_1954

.LBB0_1948:
	v_cndmask_b32_e64 v14, v10, 0, s[12:13]
	v_bfe_u32 v27, v14, 16, 1
	s_movk_i32 s18, 0x7fff
	v_mov_b32_e32 v29, 0
	v_add3_u32 v14, v14, v27, s18
	v_lshl_add_u64 v[116:117], v[44:45], 0, v[28:29]
	global_store_short_d16_hi v[116:117], v14, off offset:32
	s_cbranch_execz .LBB0_1958

.LBB0_1950:
	v_cndmask_b32_e64 v10, v6, 0, s[12:13]
	v_bfe_u32 v14, v10, 16, 1
	s_movk_i32 s18, 0x7fff
	v_mov_b32_e32 v29, 0
	v_add3_u32 v10, v10, v14, s18
	v_lshl_add_u64 v[116:117], v[44:45], 0, v[28:29]
	global_store_short_d16_hi v[116:117], v10, off offset:64
	s_cbranch_execz .LBB0_1962

.LBB0_1952:
	v_cndmask_b32_e64 v6, v2, 0, s[12:13]
	v_bfe_u32 v10, v6, 16, 1
	s_movk_i32 s12, 0x7fff
	v_mov_b32_e32 v29, 0
	v_add3_u32 v6, v6, v10, s12
	v_lshl_add_u64 v[44:45], v[44:45], 0, v[28:29]
	global_store_short_d16_hi v[44:45], v6, off offset:96
	s_cbranch_execnz .LBB0_1969
	s_branch .LBB0_1966

.LBB0_1954:
	s_and_saveexec_b64 s[18:19], s[16:17]
	s_cbranch_execz .LBB0_1956
	v_mov_b32_e32 v27, 0
	v_lshl_add_u64 v[116:117], v[46:47], 0, v[26:27]
	global_store_dword v[116:117], v14, off

.LBB0_1958:
	s_and_saveexec_b64 s[18:19], s[16:17]
	s_cbranch_execz .LBB0_1960
	v_mov_b32_e32 v27, 0
	v_lshl_add_u64 v[116:117], v[46:47], 0, v[26:27]
	global_store_dword v[116:117], v10, off offset:64

.LBB0_1962:
	s_and_saveexec_b64 s[18:19], s[16:17]
	s_cbranch_execz .LBB0_1964
	v_mov_b32_e32 v27, 0
	v_lshl_add_u64 v[116:117], v[46:47], 0, v[26:27]
	global_store_dword v[116:117], v6, off offset:128

.LBB0_1966:
	s_and_saveexec_b64 s[12:13], s[16:17]
	s_cbranch_execz .LBB0_1968
	v_mov_b32_e32 v27, 0
	v_lshl_add_u64 v[44:45], v[46:47], 0, v[26:27]
	global_store_dword v[44:45], v2, off offset:192

.LBB0_1969:
	s_movk_i32 s12, 0xfc
	v_cmp_lt_i32_e32 vcc, s12, v115
	v_lshl_add_u64 v[36:37], s[66:67], 0, v[36:37]
	s_mov_b64 s[16:17], 0x28800080
	s_and_b64 s[12:13], s[14:15], vcc
	s_mov_b64 s[20:21], -1
	v_lshl_add_u64 v[36:37], v[36:37], 0, s[16:17]
	v_lshl_add_u64 v[38:39], v[42:43], 0, v[38:39]
	s_and_b64 vcc, exec, s[6:7]
	s_mov_b64 s[18:19], 0x6600100
	s_cbranch_vccnz .LBB0_1977
	v_cndmask_b32_e64 v2, v15, 0, s[12:13]
	v_bfe_u32 v6, v2, 16, 1
	s_movk_i32 s16, 0x7fff
	v_mov_b32_e32 v29, 0
	v_add3_u32 v2, v2, v6, s16
	v_lshl_add_u64 v[44:45], v[36:37], 0, v[28:29]
	global_store_short_d16_hi v[44:45], v2, off
	s_xor_b64 s[16:17], s[12:13], -1
	v_lshl_add_u64 v[38:39], v[38:39], 0, s[18:19]
	s_cbranch_execz .LBB0_1978

.LBB0_1972:
	v_cndmask_b32_e64 v2, v11, 0, s[12:13]
	v_bfe_u32 v6, v2, 16, 1
	s_movk_i32 s18, 0x7fff
	v_mov_b32_e32 v31, 0
	v_add3_u32 v2, v2, v6, s18
	v_lshl_add_u64 v[14:15], v[36:37], 0, v[30:31]
	global_store_short_d16_hi v[14:15], v2, off
	s_cbranch_execz .LBB0_1982

.LBB0_1974:
	v_cndmask_b32_e64 v2, v7, 0, s[12:13]
	v_bfe_u32 v6, v2, 16, 1
	s_movk_i32 s18, 0x7fff
	v_mov_b32_e32 v33, 0
	v_add3_u32 v2, v2, v6, s18
	v_lshl_add_u64 v[10:11], v[36:37], 0, v[32:33]
	global_store_short_d16_hi v[10:11], v2, off
	s_cbranch_execz .LBB0_1986

.LBB0_1976:
	v_cndmask_b32_e64 v2, v3, 0, s[12:13]
	v_bfe_u32 v6, v2, 16, 1
	s_movk_i32 s12, 0x7fff
	v_mov_b32_e32 v35, 0
	v_add3_u32 v2, v2, v6, s12
	v_lshl_add_u64 v[6:7], v[36:37], 0, v[34:35]
	global_store_short_d16_hi v[6:7], v2, off
	s_cbranch_execnz .LBB0_1993
	s_branch .LBB0_1990

.LBB0_1978:
	s_and_saveexec_b64 s[18:19], s[16:17]
	s_cbranch_execz .LBB0_1980
	v_mov_b32_e32 v27, 0
	v_lshl_add_u64 v[44:45], v[38:39], 0, v[26:27]
	global_store_dword v[44:45], v15, off

.LBB0_1982:
	s_and_saveexec_b64 s[18:19], s[16:17]
	s_cbranch_execz .LBB0_1984
	v_lshlrev_b32_e32 v14, 2, v109
	v_mov_b32_e32 v15, 0
	v_lshl_add_u64 v[14:15], v[38:39], 0, v[14:15]
	global_store_dword v[14:15], v11, off

.LBB0_1986:
	s_and_saveexec_b64 s[18:19], s[16:17]
	s_cbranch_execz .LBB0_1988
	v_lshlrev_b32_e32 v10, 2, v110
	v_mov_b32_e32 v11, 0
	v_lshl_add_u64 v[10:11], v[38:39], 0, v[10:11]
	global_store_dword v[10:11], v7, off

.LBB0_1990:
	s_and_saveexec_b64 s[12:13], s[16:17]
	s_cbranch_execz .LBB0_1992
	v_lshlrev_b32_e32 v6, 2, v111
	v_mov_b32_e32 v7, 0
	v_lshl_add_u64 v[6:7], v[38:39], 0, v[6:7]
	global_store_dword v[6:7], v3, off

.LBB0_1993:
	v_or_b32_e32 v2, 2, v115
	v_ashrrev_i32_e32 v6, 1, v2
	s_movk_i32 s12, 0xfd
	v_cmp_lt_i32_e32 vcc, s12, v2
	v_add_u32_e32 v2, s28, v6
	v_ashrrev_i32_e32 v3, 31, v2
	v_lshlrev_b64 v[2:3], 8, v[2:3]
	v_ashrrev_i32_e32 v7, 31, v6
	s_and_b64 s[12:13], s[14:15], vcc
	s_mov_b64 s[18:19], -1
	v_lshl_add_u64 v[2:3], s[64:65], 0, v[2:3]
	s_and_b64 vcc, exec, s[6:7]
	v_lshlrev_b64 v[6:7], 9, v[6:7]
	s_cbranch_vccnz .LBB0_2001
	v_cndmask_b32_e64 v10, v16, 0, s[12:13]
	v_bfe_u32 v11, v10, 16, 1
	s_movk_i32 s16, 0x7fff
	v_mov_b32_e32 v29, 0
	v_add3_u32 v14, v10, v11, s16
	v_lshl_add_u64 v[10:11], v[2:3], 0, v[28:29]
	global_store_short_d16_hi v[10:11], v14, off
	s_xor_b64 s[16:17], s[12:13], -1
	v_lshl_add_u64 v[6:7], v[40:41], 0, v[6:7]
	s_cbranch_execz .LBB0_2002

.LBB0_1996:
	v_cndmask_b32_e64 v10, v12, 0, s[12:13]
	v_bfe_u32 v11, v10, 16, 1
	s_movk_i32 s18, 0x7fff
	v_mov_b32_e32 v29, 0
	v_add3_u32 v14, v10, v11, s18
	v_lshl_add_u64 v[10:11], v[2:3], 0, v[28:29]
	global_store_short_d16_hi v[10:11], v14, off offset:32
	s_cbranch_execz .LBB0_2006

.LBB0_1998:
	v_cndmask_b32_e64 v10, v8, 0, s[12:13]
	v_bfe_u32 v11, v10, 16, 1
	s_movk_i32 s18, 0x7fff
	v_mov_b32_e32 v29, 0
	v_add3_u32 v12, v10, v11, s18
	v_lshl_add_u64 v[10:11], v[2:3], 0, v[28:29]
	global_store_short_d16_hi v[10:11], v12, off offset:64
	s_cbranch_execz .LBB0_2010

.LBB0_2000:
	v_cndmask_b32_e64 v8, v4, 0, s[12:13]
	v_bfe_u32 v10, v8, 16, 1
	s_movk_i32 s12, 0x7fff
	v_mov_b32_e32 v29, 0
	v_add3_u32 v8, v8, v10, s12
	v_lshl_add_u64 v[2:3], v[2:3], 0, v[28:29]
	global_store_short_d16_hi v[2:3], v8, off offset:96
	s_cbranch_execnz .LBB0_2017
	s_branch .LBB0_2014

.LBB0_2002:
	s_and_saveexec_b64 s[18:19], s[16:17]
	s_cbranch_execz .LBB0_2004
	v_mov_b32_e32 v27, 0
	v_lshl_add_u64 v[10:11], v[6:7], 0, v[26:27]
	global_store_dword v[10:11], v16, off

.LBB0_2006:
	s_and_saveexec_b64 s[18:19], s[16:17]
	s_cbranch_execz .LBB0_2008
	v_mov_b32_e32 v27, 0
	v_lshl_add_u64 v[10:11], v[6:7], 0, v[26:27]
	global_store_dword v[10:11], v12, off offset:64

.LBB0_2010:
	s_and_saveexec_b64 s[18:19], s[16:17]
	s_cbranch_execz .LBB0_2012
	v_mov_b32_e32 v27, 0
	v_lshl_add_u64 v[10:11], v[6:7], 0, v[26:27]
	global_store_dword v[10:11], v8, off offset:128

.LBB0_2014:
	s_and_saveexec_b64 s[12:13], s[16:17]
	s_cbranch_execz .LBB0_2016
	v_mov_b32_e32 v27, 0
	v_lshl_add_u64 v[2:3], v[6:7], 0, v[26:27]
	global_store_dword v[2:3], v4, off offset:192

.LBB0_2017:
	v_or_b32_e32 v2, 3, v115
	v_ashrrev_i32_e32 v6, 1, v2
	s_movk_i32 s12, 0xfd
	v_cmp_lt_i32_e32 vcc, s12, v2
	v_add_u32_e32 v2, s28, v6
	v_ashrrev_i32_e32 v3, 31, v2
	v_lshlrev_b64 v[2:3], 8, v[2:3]
	v_ashrrev_i32_e32 v7, 31, v6
	s_and_b64 s[12:13], s[14:15], vcc
	v_lshl_add_u64 v[2:3], s[66:67], 0, v[2:3]
	s_mov_b64 s[14:15], 0x28800080
	v_lshlrev_b64 v[6:7], 9, v[6:7]
	s_mov_b64 s[16:17], -1
	v_lshl_add_u64 v[2:3], v[2:3], 0, s[14:15]
	v_lshl_add_u64 v[6:7], v[42:43], 0, v[6:7]
	s_and_b64 vcc, exec, s[6:7]
	s_mov_b64 s[18:19], 0x6600100
	s_cbranch_vccnz .LBB0_2025
	v_cndmask_b32_e64 v4, v17, 0, s[12:13]
	v_bfe_u32 v8, v4, 16, 1
	s_movk_i32 s14, 0x7fff
	v_mov_b32_e32 v29, 0
	v_add3_u32 v4, v4, v8, s14
	v_lshl_add_u64 v[10:11], v[2:3], 0, v[28:29]
	global_store_short_d16_hi v[10:11], v4, off
	s_xor_b64 s[14:15], s[12:13], -1
	v_lshl_add_u64 v[6:7], v[6:7], 0, s[18:19]
	s_cbranch_execz .LBB0_2026

.LBB0_2020:
	v_cndmask_b32_e64 v4, v13, 0, s[12:13]
	v_bfe_u32 v8, v4, 16, 1
	s_movk_i32 s16, 0x7fff
	v_mov_b32_e32 v31, 0
	v_add3_u32 v4, v4, v8, s16
	v_lshl_add_u64 v[10:11], v[2:3], 0, v[30:31]
	global_store_short_d16_hi v[10:11], v4, off
	s_cbranch_execz .LBB0_2030

.LBB0_2022:
	v_cndmask_b32_e64 v4, v9, 0, s[12:13]
	v_bfe_u32 v8, v4, 16, 1
	s_movk_i32 s16, 0x7fff
	v_mov_b32_e32 v33, 0
	v_add3_u32 v4, v4, v8, s16
	v_lshl_add_u64 v[10:11], v[2:3], 0, v[32:33]
	global_store_short_d16_hi v[10:11], v4, off
	s_cbranch_execz .LBB0_2034

.LBB0_2024:
	v_cndmask_b32_e64 v4, v5, 0, s[12:13]
	v_bfe_u32 v8, v4, 16, 1
	s_movk_i32 s6, 0x7fff
	v_mov_b32_e32 v35, 0
	v_add3_u32 v4, v4, v8, s6
	v_lshl_add_u64 v[2:3], v[2:3], 0, v[34:35]
	global_store_short_d16_hi v[2:3], v4, off
	s_cbranch_execnz .LBB0_2041
	s_branch .LBB0_2038

.LBB0_2026:
	s_and_saveexec_b64 s[16:17], s[14:15]
	s_cbranch_execz .LBB0_2028
	v_mov_b32_e32 v27, 0
	v_lshl_add_u64 v[10:11], v[6:7], 0, v[26:27]
	global_store_dword v[10:11], v17, off

.LBB0_2030:
	s_and_saveexec_b64 s[16:17], s[14:15]
	s_cbranch_execz .LBB0_2032
	v_lshlrev_b32_e32 v10, 2, v109
	v_mov_b32_e32 v11, 0
	v_lshl_add_u64 v[10:11], v[6:7], 0, v[10:11]
	global_store_dword v[10:11], v13, off

.LBB0_2034:
	s_and_saveexec_b64 s[16:17], s[14:15]
	s_cbranch_execz .LBB0_2036
	v_lshlrev_b32_e32 v10, 2, v110
	v_mov_b32_e32 v11, 0
	v_lshl_add_u64 v[10:11], v[6:7], 0, v[10:11]
	global_store_dword v[10:11], v9, off

.LBB0_2038:
	s_and_saveexec_b64 s[6:7], s[14:15]
	s_cbranch_execz .LBB0_2040
	v_lshlrev_b32_e32 v2, 2, v111
	v_mov_b32_e32 v3, 0
	v_lshl_add_u64 v[2:3], v[6:7], 0, v[2:3]
	global_store_dword v[2:3], v5, off

.LBB0_2041:
	s_bfe_u32 s6, s40, 0x30001
	s_cmp_eq_u32 s6, s3
	s_cselect_b64 s[12:13], -1, 0
	s_cmp_lg_u32 s6, s3
	s_cbranch_scc1 .LBB0_2043
	s_ashr_i32 s6, s40, 4
	s_lshr_b32 s3, s40, 1
	s_and_b32 s7, s6, -2
	s_or_b32 s5, s7, s5
	s_lshl_b32 s3, s3, 4
	s_add_i32 s6, s5, 0x100
	s_and_b32 s8, s3, 0xf0
	s_cmpk_gt_i32 s7, 0xff0e
	s_cselect_b64 s[14:15], -1, 0
	s_and_b32 s3, s40, 0x60
	s_cmpk_eq_i32 s3, 0x60
	s_cselect_b64 s[16:17], -1, 0
	s_ashr_i32 s7, s6, 31
	s_or_b64 s[14:15], s[16:17], s[14:15]
	s_lshl_b64 s[16:17], s[6:7], 18
	s_add_u32 s2, s2, s16
	s_addc_u32 s3, s4, s17
	s_add_u32 s7, s2, 0x80000
	s_addc_u32 s18, s3, 0
	s_lshl_b32 s4, s8, 10
	s_add_u32 s16, s2, s4
	s_addc_u32 s17, s3, 0
	s_add_u32 s4, s2, 0x80400
	s_addc_u32 s5, s3, 0
	s_add_u32 s20, s16, 0x1000
	s_addc_u32 s21, s17, 0
	s_add_u32 s22, s16, 0x1400
	s_addc_u32 s23, s17, 0
	v_add_u32_e32 v2, 64, v132
	v_mov_b32_e32 v3, 0
	s_add_u32 s24, s16, 0x1800
	v_lshl_add_u64 v[4:5], s[16:17], 0, v[24:25]
	v_lshl_add_u64 v[6:7], s[20:21], 0, v[24:25]
	s_addc_u32 s25, s17, 0
	v_lshlrev_b64 v[2:3], 2, v[2:3]
	global_load_dword v20, v[4:5], off
	global_load_dword v21, v[4:5], off offset:256
	global_load_dword v22, v[4:5], off offset:2560
	global_load_dword v23, v[4:5], off offset:2816
	global_load_dword v107, v[4:5], off offset:1024
	global_load_dword v105, v[4:5], off offset:1280
	global_load_dword v103, v[4:5], off offset:2048
	global_load_dword v100, v[4:5], off offset:2304
	v_lshl_add_u64 v[8:9], s[22:23], 0, v[24:25]
	global_load_dword v108, v[4:5], off offset:3584
	global_load_dword v106, v[4:5], off offset:3840
	global_load_dword v104, v[6:7], off offset:512
	global_load_dword v102, v[6:7], off offset:768
	global_load_dword v98, v[4:5], off offset:3072
	global_load_dword v90, v[8:9], off
	global_load_dword v94, v[6:7], off
	global_load_dword v97, v[4:5], off offset:3328
	v_lshl_add_u64 v[6:7], s[20:21], 0, v[2:3]
	s_add_u32 s20, s16, 0x1c00
	s_addc_u32 s21, s17, 0
	v_lshl_add_u64 v[12:13], s[22:23], 0, v[2:3]
	s_add_u32 s22, s16, 0x2000
	s_addc_u32 s23, s17, 0
	v_lshl_add_u64 v[10:11], s[24:25], 0, v[24:25]
	v_lshl_add_u64 v[14:15], s[20:21], 0, v[24:25]
	global_load_dword v101, v[8:9], off offset:512
	global_load_dword v99, v[8:9], off offset:768
	global_load_dword v93, v[6:7], off
	global_load_dword v96, v[10:11], off offset:512
	global_load_dword v95, v[10:11], off offset:768
	global_load_dword v89, v[12:13], off
	global_load_dword v82, v[14:15], off
	global_load_dword v87, v[10:11], off
	v_lshl_add_u64 v[6:7], s[24:25], 0, v[2:3]
	s_add_u32 s24, s16, 0x2400
	s_addc_u32 s25, s17, 0
	v_lshl_add_u64 v[10:11], s[20:21], 0, v[2:3]
	s_add_u32 s20, s16, 0x2800
	s_addc_u32 s21, s17, 0
	v_lshl_add_u64 v[8:9], s[22:23], 0, v[24:25]
	v_lshl_add_u64 v[12:13], s[24:25], 0, v[24:25]
	global_load_dword v92, v[14:15], off offset:512
	global_load_dword v91, v[14:15], off offset:768
	global_load_dword v85, v[6:7], off
	global_load_dword v88, v[8:9], off offset:512
	global_load_dword v86, v[8:9], off offset:768
	global_load_dword v81, v[10:11], off
	global_load_dword v73, v[12:13], off
	global_load_dword v79, v[8:9], off
	v_lshl_add_u64 v[6:7], s[22:23], 0, v[2:3]
	s_add_u32 s22, s16, 0x2c00
	s_addc_u32 s23, s17, 0
	v_lshl_add_u64 v[10:11], s[24:25], 0, v[2:3]
	s_add_u32 s24, s16, 0x3000
	s_addc_u32 s25, s17, 0
	v_lshl_add_u64 v[8:9], s[20:21], 0, v[24:25]
	v_lshl_add_u64 v[14:15], s[22:23], 0, v[24:25]
	global_load_dword v84, v[12:13], off offset:512
	global_load_dword v83, v[12:13], off offset:768
	global_load_dword v77, v[6:7], off
	global_load_dword v80, v[8:9], off offset:512
	global_load_dword v78, v[8:9], off offset:768
	global_load_dword v72, v[10:11], off
	global_load_dword v65, v[14:15], off
	global_load_dword v70, v[8:9], off
	v_lshl_add_u64 v[6:7], s[20:21], 0, v[2:3]
	s_add_u32 s20, s16, 0x3400
	s_addc_u32 s21, s17, 0
	v_lshl_add_u64 v[10:11], s[22:23], 0, v[2:3]
	s_add_u32 s22, s16, 0x3800
	s_addc_u32 s23, s17, 0
	v_lshl_add_u64 v[8:9], s[24:25], 0, v[24:25]
	v_lshl_add_u64 v[12:13], s[20:21], 0, v[24:25]
	global_load_dword v76, v[14:15], off offset:512
	global_load_dword v74, v[14:15], off offset:768
	global_load_dword v68, v[6:7], off
	global_load_dword v71, v[8:9], off offset:512
	global_load_dword v69, v[8:9], off offset:768
	global_load_dword v64, v[10:11], off
	global_load_dword v56, v[12:13], off
	global_load_dword v62, v[8:9], off
	v_lshl_add_u64 v[10:11], s[20:21], 0, v[2:3]
	s_mov_b64 s[20:21], 0x3c00
	s_add_u32 s19, s16, 0x4000
	v_lshl_add_u64 v[14:15], v[4:5], 0, s[20:21]
	s_addc_u32 s20, s17, 0
	s_and_b64 s[16:17], s[14:15], exec
	s_cselect_b32 s7, s22, s7
	s_cselect_b32 s16, s23, s18
	s_cmpk_eq_i32 s8, 0xf0
	v_lshl_add_u64 v[6:7], s[24:25], 0, v[2:3]
	s_cselect_b32 s17, s16, s20
	s_cselect_b32 s16, s7, s19
	v_lshl_add_u64 v[2:3], s[22:23], 0, v[2:3]
	s_or_b32 s7, s8, 15
	v_lshl_add_u64 v[8:9], s[22:23], 0, v[24:25]
	global_load_dword v67, v[12:13], off offset:512
	global_load_dword v66, v[12:13], off offset:768
	global_load_dword v60, v[6:7], off
	global_load_dword v63, v[8:9], off offset:512
	global_load_dword v61, v[8:9], off offset:768
	global_load_dword v55, v[10:11], off
	global_load_dword v59, v[14:15], off offset:512
	global_load_dword v53, v[8:9], off
	global_load_dword v57, v[14:15], off offset:768
	global_load_dword v51, v[2:3], off
	v_lshl_add_u64 v[2:3], s[16:17], 0, v[24:25]
	s_lshl_b32 s16, s7, 10
	s_add_u32 s2, s2, s16
	s_addc_u32 s3, s3, 0
	s_add_u32 s16, s2, 0x800
	s_addc_u32 s17, s3, 0
	s_and_b64 s[14:15], s[14:15], exec
	global_load_dword v54, v[2:3], off offset:512
	global_load_dword v52, v[2:3], off offset:768
	s_cselect_b32 s4, s2, s4
	s_cselect_b32 s5, s3, s5
	s_cmpk_lt_u32 s7, 0xfe
	v_add_co_u32_e32 v2, vcc, 0x3000, v4
	s_cselect_b32 s5, s17, s5
	s_cselect_b32 s4, s16, s4
	v_addc_co_u32_e32 v3, vcc, 0, v5, vcc
	v_lshl_add_u64 v[4:5], s[2:3], 0, v[24:25]
	global_load_dword v49, v[2:3], off offset:3072
	global_load_dword v1, v[4:5], off offset:256
	v_lshl_add_u64 v[2:3], s[4:5], 0, v[24:25]
	global_load_dword v50, v[2:3], off offset:512
	global_load_dword v48, v[2:3], off offset:768
	s_andn2_b64 vcc, exec, s[12:13]
	s_cbranch_vccz .LBB0_2044
	s_branch .LBB0_2204

.LBB0_2107:
	v_add_u32_e32 v1, s4, v114
	ds_read2_b32 v[18:19], v113 offset1:16
	ds_read2_b32 v[20:21], v1 offset1:4
	v_add_u32_e32 v22, 0x800, v113
	s_add_i32 s4, s4, 64
	s_cmpk_lg_i32 s4, 0x200
	s_waitcnt lgkmcnt(0)
	v_mfma_f32_16x16x4_f32 v[14:17], v20, v18, v[14:17]
	v_mfma_f32_16x16x4_f32 v[10:13], v20, v19, v[10:13]
	ds_read2_b32 v[18:19], v113 offset0:32 offset1:48
	s_waitcnt lgkmcnt(0)
	v_mfma_f32_16x16x4_f32 v[6:9], v20, v18, v[6:9]
	v_mfma_f32_16x16x4_f32 v[2:5], v20, v19, v[2:5]
	v_add_u32_e32 v20, 0x400, v113
	ds_read2_b32 v[18:19], v20 offset1:16
	s_waitcnt lgkmcnt(0)
	v_mfma_f32_16x16x4_f32 v[14:17], v21, v18, v[14:17]
	v_mfma_f32_16x16x4_f32 v[10:13], v21, v19, v[10:13]
	ds_read2_b32 v[18:19], v20 offset0:32 offset1:48
	s_waitcnt lgkmcnt(0)
	v_mfma_f32_16x16x4_f32 v[6:9], v21, v18, v[6:9]
	v_mfma_f32_16x16x4_f32 v[2:5], v21, v19, v[2:5]
	ds_read2_b32 v[18:19], v1 offset0:8 offset1:12
	ds_read2_b32 v[20:21], v22 offset1:16
	v_add_u32_e32 v1, 0xc00, v113
	v_add_u32_e32 v113, 0x1000, v113
	s_waitcnt lgkmcnt(0)
	v_mfma_f32_16x16x4_f32 v[14:17], v18, v20, v[14:17]
	v_mfma_f32_16x16x4_f32 v[10:13], v18, v21, v[10:13]
	ds_read2_b32 v[20:21], v22 offset0:32 offset1:48
	s_waitcnt lgkmcnt(0)
	v_mfma_f32_16x16x4_f32 v[6:9], v18, v20, v[6:9]
	v_mfma_f32_16x16x4_f32 v[2:5], v18, v21, v[2:5]
	ds_read2_b32 v[20:21], v1 offset1:16
	s_waitcnt lgkmcnt(0)
	v_mfma_f32_16x16x4_f32 v[14:17], v19, v20, v[14:17]
	v_mfma_f32_16x16x4_f32 v[10:13], v19, v21, v[10:13]
	ds_read2_b32 v[20:21], v1 offset0:32 offset1:48
	s_waitcnt lgkmcnt(0)
	v_mfma_f32_16x16x4_f32 v[6:9], v19, v20, v[6:9]
	v_mfma_f32_16x16x4_f32 v[2:5], v19, v21, v[2:5]
	s_cbranch_scc1 .LBB0_2107
	s_ashr_i32 s4, s6, 3
	s_lshl_b32 s3, s3, 7
	s_ashr_i32 s5, s4, 31
	v_add_u32_e32 v1, s8, v112
	s_add_u32 s4, s4, s9
	v_add3_u32 v38, s2, -8, v58
	s_movk_i32 s2, 0xfd
	s_addc_u32 s5, s5, 0
	v_ashrrev_i32_e32 v24, 1, v1
	v_cmp_lt_i32_e32 vcc, s2, v1
	s_lshl_b64 s[16:17], s[4:5], 17
	s_and_b64 s[18:19], vcc, s[12:13]
	v_add_u32_e32 v18, s3, v24
	s_waitcnt lgkmcnt(0)
	v_mov_b32_e32 v39, 0
	v_ashrrev_i32_e32 v19, 31, v18
	s_add_u32 s8, s26, s16
	v_lshlrev_b64 v[20:21], 16, v[38:39]
	s_addc_u32 s9, s27, s17
	v_lshlrev_b64 v[22:23], 8, v[18:19]
	v_ashrrev_i32_e32 v25, 31, v24
	v_cndmask_b32_e64 v27, 0, 1, s[14:15]
	s_mov_b64 s[20:21], -1
	v_lshl_add_u64 v[36:37], s[8:9], 0, v[22:23]
	v_lshl_add_u64 v[18:19], s[10:11], 0, v[20:21]
	v_cmp_ne_u32_e64 s[6:7], 1, v27
	s_andn2_b64 vcc, exec, s[14:15]
	v_lshlrev_b64 v[24:25], 9, v[24:25]
	s_cbranch_vccnz .LBB0_2116
	v_cndmask_b32_e64 v27, v14, 0, s[18:19]
	v_bfe_u32 v29, v27, 16, 1
	s_movk_i32 s2, 0x7fff
	v_add3_u32 v27, v27, v29, s2
	v_mov_b32_e32 v29, v39
	v_lshl_add_u64 v[38:39], v[36:37], 0, v[28:29]
	global_store_short_d16_hi v[38:39], v27, off
	s_xor_b64 s[10:11], s[18:19], -1
	v_lshl_add_u64 v[38:39], v[18:19], 0, v[24:25]
	s_cbranch_execz .LBB0_2117

.LBB0_2111:
	v_cndmask_b32_e64 v14, v10, 0, s[18:19]
	v_bfe_u32 v27, v14, 16, 1
	s_movk_i32 s2, 0x7fff
	v_mov_b32_e32 v29, 0
	v_add3_u32 v14, v14, v27, s2
	v_lshl_add_u64 v[40:41], v[36:37], 0, v[28:29]
	global_store_short_d16_hi v[40:41], v14, off offset:32
	s_cbranch_execz .LBB0_2121

.LBB0_2113:
	v_cndmask_b32_e64 v10, v6, 0, s[18:19]
	v_bfe_u32 v14, v10, 16, 1
	s_movk_i32 s2, 0x7fff
	v_mov_b32_e32 v29, 0
	v_add3_u32 v10, v10, v14, s2
	v_lshl_add_u64 v[40:41], v[36:37], 0, v[28:29]
	global_store_short_d16_hi v[40:41], v10, off offset:64
	s_cbranch_execz .LBB0_2125

.LBB0_2115:
	v_cndmask_b32_e64 v6, v2, 0, s[18:19]
	v_bfe_u32 v10, v6, 16, 1
	s_movk_i32 s2, 0x7fff
	v_mov_b32_e32 v29, 0
	v_add3_u32 v6, v6, v10, s2
	v_lshl_add_u64 v[36:37], v[36:37], 0, v[28:29]
	global_store_short_d16_hi v[36:37], v6, off offset:96
	s_cbranch_execnz .LBB0_2132
	s_branch .LBB0_2129

.LBB0_2117:
	s_and_saveexec_b64 s[14:15], s[10:11]
	s_cbranch_execz .LBB0_2119
	v_mov_b32_e32 v27, 0
	v_lshl_add_u64 v[40:41], v[38:39], 0, v[26:27]
	global_store_dword v[40:41], v14, off

.LBB0_2121:
	s_and_saveexec_b64 s[14:15], s[10:11]
	s_cbranch_execz .LBB0_2123
	v_mov_b32_e32 v27, 0
	v_lshl_add_u64 v[40:41], v[38:39], 0, v[26:27]
	global_store_dword v[40:41], v10, off offset:64

.LBB0_2125:
	s_and_saveexec_b64 s[14:15], s[10:11]
	s_cbranch_execz .LBB0_2127
	v_mov_b32_e32 v27, 0
	v_lshl_add_u64 v[40:41], v[38:39], 0, v[26:27]
	global_store_dword v[40:41], v6, off offset:128

.LBB0_2129:
	s_and_saveexec_b64 s[14:15], s[10:11]
	s_cbranch_execz .LBB0_2131
	v_mov_b32_e32 v27, 0
	v_lshl_add_u64 v[36:37], v[38:39], 0, v[26:27]
	global_store_dword v[36:37], v2, off offset:192

.LBB0_2132:
	s_movk_i32 s2, 0xfc
	v_cmp_lt_i32_e32 vcc, s2, v1
	s_and_b64 s[14:15], vcc, s[12:13]
	s_add_u32 s10, s38, s16
	s_addc_u32 s11, s39, s17
	v_lshl_add_u64 v[22:23], s[10:11], 0, v[22:23]
	s_mov_b64 s[4:5], 0x28800080
	v_lshl_add_u64 v[20:21], s[38:39], 0, v[20:21]
	s_mov_b64 s[18:19], -1
	v_lshl_add_u64 v[22:23], v[22:23], 0, s[4:5]
	v_lshl_add_u64 v[24:25], v[20:21], 0, v[24:25]
	s_and_b64 vcc, exec, s[6:7]
	s_mov_b64 s[20:21], 0x6600100
	s_cbranch_vccnz .LBB0_2140
	v_cndmask_b32_e64 v2, v15, 0, s[14:15]
	v_bfe_u32 v6, v2, 16, 1
	s_movk_i32 s2, 0x7fff
	v_mov_b32_e32 v29, 0
	v_add3_u32 v2, v2, v6, s2
	v_lshl_add_u64 v[36:37], v[22:23], 0, v[28:29]
	global_store_short_d16_hi v[36:37], v2, off
	s_xor_b64 s[16:17], s[14:15], -1
	v_lshl_add_u64 v[24:25], v[24:25], 0, s[20:21]
	s_cbranch_execz .LBB0_2141

.LBB0_2135:
	v_cndmask_b32_e64 v2, v11, 0, s[14:15]
	v_bfe_u32 v6, v2, 16, 1
	s_movk_i32 s2, 0x7fff
	v_mov_b32_e32 v31, 0
	v_add3_u32 v2, v2, v6, s2
	v_lshl_add_u64 v[14:15], v[22:23], 0, v[30:31]
	global_store_short_d16_hi v[14:15], v2, off
	s_cbranch_execz .LBB0_2145

.LBB0_2137:
	v_cndmask_b32_e64 v2, v7, 0, s[14:15]
	v_bfe_u32 v6, v2, 16, 1
	s_movk_i32 s2, 0x7fff
	v_mov_b32_e32 v33, 0
	v_add3_u32 v2, v2, v6, s2
	v_lshl_add_u64 v[10:11], v[22:23], 0, v[32:33]
	global_store_short_d16_hi v[10:11], v2, off
	s_cbranch_execz .LBB0_2149

.LBB0_2139:
	v_cndmask_b32_e64 v2, v3, 0, s[14:15]
	v_bfe_u32 v6, v2, 16, 1
	s_movk_i32 s2, 0x7fff
	v_mov_b32_e32 v35, 0
	v_add3_u32 v2, v2, v6, s2
	v_lshl_add_u64 v[6:7], v[22:23], 0, v[34:35]
	global_store_short_d16_hi v[6:7], v2, off
	s_cbranch_execnz .LBB0_2156
	s_branch .LBB0_2153

.LBB0_2141:
	s_and_saveexec_b64 s[18:19], s[16:17]
	s_cbranch_execz .LBB0_2143
	v_mov_b32_e32 v27, 0
	v_lshl_add_u64 v[36:37], v[24:25], 0, v[26:27]
	global_store_dword v[36:37], v15, off

.LBB0_2145:
	s_and_saveexec_b64 s[18:19], s[16:17]
	s_cbranch_execz .LBB0_2147
	v_lshlrev_b32_e32 v14, 2, v109
	v_mov_b32_e32 v15, 0
	v_lshl_add_u64 v[14:15], v[24:25], 0, v[14:15]
	global_store_dword v[14:15], v11, off

.LBB0_2149:
	s_and_saveexec_b64 s[18:19], s[16:17]
	s_cbranch_execz .LBB0_2151
	v_lshlrev_b32_e32 v10, 2, v110
	v_mov_b32_e32 v11, 0
	v_lshl_add_u64 v[10:11], v[24:25], 0, v[10:11]
	global_store_dword v[10:11], v7, off

.LBB0_2153:
	s_and_saveexec_b64 s[14:15], s[16:17]
	s_cbranch_execz .LBB0_2155
	v_lshlrev_b32_e32 v6, 2, v111
	v_mov_b32_e32 v7, 0
	v_lshl_add_u64 v[6:7], v[24:25], 0, v[6:7]
	global_store_dword v[6:7], v3, off

.LBB0_2156:
	v_or_b32_e32 v2, 2, v1
	v_ashrrev_i32_e32 v6, 1, v2
	s_movk_i32 s2, 0xfd
	v_cmp_lt_i32_e32 vcc, s2, v2
	v_add_u32_e32 v2, s3, v6
	v_ashrrev_i32_e32 v3, 31, v2
	v_lshlrev_b64 v[2:3], 8, v[2:3]
	v_ashrrev_i32_e32 v7, 31, v6
	s_and_b64 s[14:15], vcc, s[12:13]
	s_mov_b64 s[16:17], -1
	v_lshl_add_u64 v[2:3], s[8:9], 0, v[2:3]
	s_and_b64 vcc, exec, s[6:7]
	v_lshlrev_b64 v[6:7], 9, v[6:7]
	s_cbranch_vccnz .LBB0_2164
	v_cndmask_b32_e64 v10, v16, 0, s[14:15]
	v_bfe_u32 v11, v10, 16, 1
	s_movk_i32 s2, 0x7fff
	v_mov_b32_e32 v29, 0
	v_add3_u32 v14, v10, v11, s2
	v_lshl_add_u64 v[10:11], v[2:3], 0, v[28:29]
	global_store_short_d16_hi v[10:11], v14, off
	s_xor_b64 s[8:9], s[14:15], -1
	v_lshl_add_u64 v[6:7], v[18:19], 0, v[6:7]
	s_cbranch_execz .LBB0_2165

.LBB0_2159:
	v_cndmask_b32_e64 v10, v12, 0, s[14:15]
	v_bfe_u32 v11, v10, 16, 1
	s_movk_i32 s2, 0x7fff
	v_mov_b32_e32 v29, 0
	v_add3_u32 v14, v10, v11, s2
	v_lshl_add_u64 v[10:11], v[2:3], 0, v[28:29]
	global_store_short_d16_hi v[10:11], v14, off offset:32
	s_cbranch_execz .LBB0_2169

.LBB0_2161:
	v_cndmask_b32_e64 v10, v8, 0, s[14:15]
	v_bfe_u32 v11, v10, 16, 1
	s_movk_i32 s2, 0x7fff
	v_mov_b32_e32 v29, 0
	v_add3_u32 v12, v10, v11, s2
	v_lshl_add_u64 v[10:11], v[2:3], 0, v[28:29]
	global_store_short_d16_hi v[10:11], v12, off offset:64
	s_cbranch_execz .LBB0_2173

.LBB0_2163:
	v_cndmask_b32_e64 v8, v4, 0, s[14:15]
	v_bfe_u32 v10, v8, 16, 1
	s_movk_i32 s2, 0x7fff
	v_mov_b32_e32 v29, 0
	v_add3_u32 v8, v8, v10, s2
	v_lshl_add_u64 v[2:3], v[2:3], 0, v[28:29]
	global_store_short_d16_hi v[2:3], v8, off offset:96
	s_cbranch_execnz .LBB0_2180
	s_branch .LBB0_2177

.LBB0_2165:
	s_and_saveexec_b64 s[16:17], s[8:9]
	s_cbranch_execz .LBB0_2167
	v_mov_b32_e32 v27, 0
	v_lshl_add_u64 v[10:11], v[6:7], 0, v[26:27]
	global_store_dword v[10:11], v16, off

.LBB0_2169:
	s_and_saveexec_b64 s[16:17], s[8:9]
	s_cbranch_execz .LBB0_2171
	v_mov_b32_e32 v27, 0
	v_lshl_add_u64 v[10:11], v[6:7], 0, v[26:27]
	global_store_dword v[10:11], v12, off offset:64

.LBB0_2173:
	s_and_saveexec_b64 s[16:17], s[8:9]
	s_cbranch_execz .LBB0_2175
	v_mov_b32_e32 v27, 0
	v_lshl_add_u64 v[10:11], v[6:7], 0, v[26:27]
	global_store_dword v[10:11], v8, off offset:128

.LBB0_2177:
	s_and_saveexec_b64 s[14:15], s[8:9]
	s_cbranch_execz .LBB0_2179
	v_mov_b32_e32 v27, 0
	v_lshl_add_u64 v[2:3], v[6:7], 0, v[26:27]
	global_store_dword v[2:3], v4, off offset:192

.LBB0_2180:
	v_or_b32_e32 v1, 3, v1
	v_ashrrev_i32_e32 v6, 1, v1
	v_add_u32_e32 v2, s3, v6
	v_ashrrev_i32_e32 v3, 31, v2
	s_movk_i32 s2, 0xfd
	v_lshlrev_b64 v[2:3], 8, v[2:3]
	v_ashrrev_i32_e32 v7, 31, v6
	v_cmp_lt_i32_e32 vcc, s2, v1
	v_lshl_add_u64 v[2:3], s[10:11], 0, v[2:3]
	s_mov_b64 s[2:3], 0x28800080
	v_lshlrev_b64 v[6:7], 9, v[6:7]
	s_and_b64 s[8:9], vcc, s[12:13]
	s_mov_b64 s[12:13], -1
	v_lshl_add_u64 v[2:3], v[2:3], 0, s[2:3]
	v_lshl_add_u64 v[6:7], v[20:21], 0, v[6:7]
	s_and_b64 vcc, exec, s[6:7]
	s_mov_b64 s[14:15], 0x6600100
	s_cbranch_vccnz .LBB0_2188
	v_cndmask_b32_e64 v1, v17, 0, s[8:9]
	v_bfe_u32 v4, v1, 16, 1
	s_movk_i32 s2, 0x7fff
	v_mov_b32_e32 v29, 0
	v_add3_u32 v1, v1, v4, s2
	v_lshl_add_u64 v[10:11], v[2:3], 0, v[28:29]
	global_store_short_d16_hi v[10:11], v1, off
	s_xor_b64 s[10:11], s[8:9], -1
	v_lshl_add_u64 v[6:7], v[6:7], 0, s[14:15]
	s_cbranch_execz .LBB0_2189

.LBB0_2183:
	v_cndmask_b32_e64 v1, v13, 0, s[8:9]
	v_bfe_u32 v4, v1, 16, 1
	s_movk_i32 s2, 0x7fff
	v_mov_b32_e32 v31, 0
	v_add3_u32 v1, v1, v4, s2
	v_lshl_add_u64 v[10:11], v[2:3], 0, v[30:31]
	global_store_short_d16_hi v[10:11], v1, off
	s_cbranch_execz .LBB0_2193

.LBB0_2185:
	v_cndmask_b32_e64 v1, v9, 0, s[8:9]
	v_bfe_u32 v4, v1, 16, 1
	s_movk_i32 s2, 0x7fff
	v_mov_b32_e32 v33, 0
	v_add3_u32 v1, v1, v4, s2
	v_lshl_add_u64 v[10:11], v[2:3], 0, v[32:33]
	global_store_short_d16_hi v[10:11], v1, off
	s_cbranch_execz .LBB0_2197

.LBB0_2187:
	v_cndmask_b32_e64 v1, v5, 0, s[8:9]
	v_bfe_u32 v4, v1, 16, 1
	s_movk_i32 s2, 0x7fff
	v_mov_b32_e32 v35, 0
	v_add3_u32 v1, v1, v4, s2
	v_lshl_add_u64 v[2:3], v[2:3], 0, v[34:35]
	global_store_short_d16_hi v[2:3], v1, off
	s_cbranch_execnz .LBB0_2204
	s_branch .LBB0_2201

.LBB0_2189:
	s_and_saveexec_b64 s[12:13], s[10:11]
	s_cbranch_execz .LBB0_2191
	v_mov_b32_e32 v27, 0
	v_lshl_add_u64 v[10:11], v[6:7], 0, v[26:27]
	global_store_dword v[10:11], v17, off

.LBB0_2193:
	s_and_saveexec_b64 s[12:13], s[10:11]
	s_cbranch_execz .LBB0_2195
	v_lshlrev_b32_e32 v10, 2, v109
	v_mov_b32_e32 v11, 0
	v_lshl_add_u64 v[10:11], v[6:7], 0, v[10:11]
	global_store_dword v[10:11], v13, off

.LBB0_2197:
	s_and_saveexec_b64 s[12:13], s[10:11]
	s_cbranch_execz .LBB0_2199
	v_lshlrev_b32_e32 v10, 2, v110
	v_mov_b32_e32 v11, 0
	v_lshl_add_u64 v[10:11], v[6:7], 0, v[10:11]
	global_store_dword v[10:11], v9, off

.LBB0_2201:
	s_and_saveexec_b64 s[6:7], s[10:11]
	s_cbranch_execz .LBB0_2203
	v_lshlrev_b32_e32 v2, 2, v111
	v_mov_b32_e32 v3, 0
	v_lshl_add_u64 v[2:3], v[6:7], 0, v[2:3]
	global_store_dword v[2:3], v5, off

.LBB0_2262:
	v_lshl_add_u64 v[10:11], s[38:39], 0, v[8:9]
	v_add_co_u32_e32 v14, vcc, 0x22400000, v10
	v_lshl_add_u64 v[12:13], s[38:39], 0, v[6:7]
	s_nop 0
	v_addc_co_u32_e32 v15, vcc, 0, v11, vcc
	v_add_co_u32_e32 v12, vcc, 0x26400000, v12
	global_load_dword v3, v[14:15], off
	s_nop 0
	v_addc_co_u32_e32 v13, vcc, 0, v13, vcc
	v_add_co_u32_e32 v14, vcc, 0x22408000, v10
	global_load_dword v5, v[12:13], off
	global_load_dword v40, v[12:13], off offset:256
	global_load_dword v41, v[12:13], off offset:512
	global_load_dword v42, v[12:13], off offset:768
	global_load_dword v43, v[12:13], off offset:1024
	global_load_dword v44, v[12:13], off offset:1280
	global_load_dword v45, v[12:13], off offset:1536
	global_load_dword v46, v[12:13], off offset:1792
	global_load_dword v47, v[12:13], off offset:2048
	global_load_dword v48, v[12:13], off offset:2304
	global_load_dword v49, v[12:13], off offset:2560
	global_load_dword v50, v[12:13], off offset:2816
	global_load_dword v51, v[12:13], off offset:3072
	global_load_dword v52, v[12:13], off offset:3328
	global_load_dword v53, v[12:13], off offset:3584
	v_addc_co_u32_e32 v15, vcc, 0, v11, vcc
	v_add_co_u32_e32 v16, vcc, 0x22410000, v10
	s_add_i32 s2, s2, 16
	s_nop 0
	v_addc_co_u32_e32 v17, vcc, 0, v11, vcc
	v_add_co_u32_e32 v18, vcc, 0x22418000, v10
	global_load_dword v54, v[14:15], off
	global_load_dword v55, v[16:17], off
	v_addc_co_u32_e32 v19, vcc, 0, v11, vcc
	v_add_co_u32_e32 v14, vcc, 0x22420000, v10
	v_lshl_add_u64 v[6:7], v[6:7], 0, s[8:9]
	s_nop 0
	v_addc_co_u32_e32 v15, vcc, 0, v11, vcc
	v_add_co_u32_e32 v16, vcc, 0x22428000, v10
	global_load_dword v56, v[18:19], off
	global_load_dword v57, v[14:15], off
	v_addc_co_u32_e32 v17, vcc, 0, v11, vcc
	v_add_co_u32_e32 v14, vcc, 0x22430000, v10
	v_lshl_add_u64 v[8:9], v[8:9], 0, s[10:11]
	s_nop 0
	v_addc_co_u32_e32 v15, vcc, 0, v11, vcc
	v_add_co_u32_e32 v18, vcc, 0x22438000, v10
	global_load_dword v58, v[16:17], off
	global_load_dword v59, v[14:15], off
	v_addc_co_u32_e32 v19, vcc, 0, v11, vcc
	v_add_co_u32_e32 v14, vcc, 0x22440000, v10
	global_load_dword v60, v[18:19], off
	global_load_dword v61, v[12:13], off offset:3840
	v_addc_co_u32_e32 v15, vcc, 0, v11, vcc
	v_add_co_u32_e32 v16, vcc, 0x22448000, v10
	s_cmpk_lt_u32 s2, 0x70
	s_nop 0
	v_addc_co_u32_e32 v17, vcc, 0, v11, vcc
	v_add_co_u32_e32 v12, vcc, 0x22450000, v10
	global_load_dword v62, v[14:15], off
	global_load_dword v63, v[16:17], off
	v_addc_co_u32_e32 v13, vcc, 0, v11, vcc
	v_add_co_u32_e32 v14, vcc, 0x22458000, v10
	s_waitcnt vmcnt(0) lgkmcnt(0)
	v_fmac_f32_e32 v3, v1, v5
	v_addc_co_u32_e32 v15, vcc, 0, v11, vcc
	v_add_co_u32_e32 v16, vcc, 0x22460000, v10
	global_load_dword v64, v[12:13], off
	global_load_dword v65, v[14:15], off
	v_addc_co_u32_e32 v17, vcc, 0, v11, vcc
	v_add_co_u32_e32 v12, vcc, 0x22468000, v10
	v_fmac_f32_e32 v54, v3, v40
	s_nop 0
	v_addc_co_u32_e32 v13, vcc, 0, v11, vcc
	v_add_co_u32_e32 v14, vcc, 0x22470000, v10
	global_load_dword v66, v[16:17], off
	global_load_dword v67, v[12:13], off
	v_addc_co_u32_e32 v15, vcc, 0, v11, vcc
	v_add_co_u32_e32 v12, vcc, 0x22478000, v10
	v_fmac_f32_e32 v55, v54, v41
	s_nop 0
	v_addc_co_u32_e32 v13, vcc, 0, v11, vcc
	global_load_dword v68, v[14:15], off
	global_load_dword v69, v[12:13], off
	v_add_co_u32_e32 v16, vcc, 0x24400000, v10
	v_fmac_f32_e32 v56, v55, v42
	s_nop 0
	v_addc_co_u32_e32 v17, vcc, 0, v11, vcc
	v_add_co_u32_e32 v12, vcc, 0x24408000, v10
	global_store_dword v[16:17], v1, off
	s_nop 0
	v_addc_co_u32_e32 v13, vcc, 0, v11, vcc
	v_add_co_u32_e32 v14, vcc, 0x24410000, v10
	v_fmac_f32_e32 v57, v56, v43
	s_nop 0
	v_addc_co_u32_e32 v15, vcc, 0, v11, vcc
	v_add_co_u32_e32 v16, vcc, 0x24418000, v10
	v_fmac_f32_e32 v58, v57, v44
	s_nop 0
	v_addc_co_u32_e32 v17, vcc, 0, v11, vcc
	v_add_co_u32_e32 v18, vcc, 0x24420000, v10
	v_fmac_f32_e32 v59, v58, v45
	s_nop 0
	v_addc_co_u32_e32 v19, vcc, 0, v11, vcc
	v_add_co_u32_e32 v20, vcc, 0x24428000, v10
	v_fmac_f32_e32 v60, v59, v46
	s_nop 0
	v_addc_co_u32_e32 v21, vcc, 0, v11, vcc
	v_add_co_u32_e32 v22, vcc, 0x24430000, v10
	v_fmac_f32_e32 v62, v60, v47
	s_nop 0
	v_addc_co_u32_e32 v23, vcc, 0, v11, vcc
	v_add_co_u32_e32 v24, vcc, 0x24438000, v10
	v_fmac_f32_e32 v63, v62, v48
	s_nop 0
	v_addc_co_u32_e32 v25, vcc, 0, v11, vcc
	v_add_co_u32_e32 v26, vcc, 0x24440000, v10
	global_store_dword v[12:13], v3, off
	s_nop 0
	v_addc_co_u32_e32 v27, vcc, 0, v11, vcc
	v_add_co_u32_e32 v28, vcc, 0x24448000, v10
	global_store_dword v[14:15], v54, off
	s_nop 0
	v_addc_co_u32_e32 v29, vcc, 0, v11, vcc
	v_add_co_u32_e32 v30, vcc, 0x24450000, v10
	global_store_dword v[16:17], v55, off
	s_nop 0
	v_addc_co_u32_e32 v31, vcc, 0, v11, vcc
	v_add_co_u32_e32 v32, vcc, 0x24458000, v10
	s_waitcnt vmcnt(0) lgkmcnt(0)
	v_fmac_f32_e32 v64, v63, v49
	v_addc_co_u32_e32 v33, vcc, 0, v11, vcc
	v_add_co_u32_e32 v34, vcc, 0x24460000, v10
	v_fmac_f32_e32 v65, v64, v50
	s_nop 0
	v_addc_co_u32_e32 v35, vcc, 0, v11, vcc
	v_add_co_u32_e32 v36, vcc, 0x24468000, v10
	global_store_dword v[18:19], v56, off
	s_nop 0
	v_addc_co_u32_e32 v37, vcc, 0, v11, vcc
	v_add_co_u32_e32 v38, vcc, 0x24470000, v10
	v_fmac_f32_e32 v66, v65, v51
	s_nop 0
	v_addc_co_u32_e32 v39, vcc, 0, v11, vcc
	v_fmac_f32_e32 v67, v66, v52
	v_add_co_u32_e32 v10, vcc, 0x24478000, v10
	v_fmac_f32_e32 v68, v67, v53
	v_mov_b32_e32 v1, v69
	v_addc_co_u32_e32 v11, vcc, 0, v11, vcc
	v_fmac_f32_e32 v1, v68, v61
	global_store_dword v[20:21], v57, off
	global_store_dword v[22:23], v58, off
	global_store_dword v[24:25], v59, off
	global_store_dword v[26:27], v60, off
	global_store_dword v[28:29], v62, off
	global_store_dword v[30:31], v63, off
	global_store_dword v[32:33], v64, off
	global_store_dword v[34:35], v65, off
	global_store_dword v[36:37], v66, off
	global_store_dword v[38:39], v67, off
	global_store_dword v[10:11], v68, off
	s_cbranch_scc1 .LBB0_2262
	v_ashrrev_i32_e32 v5, 31, v4
	v_readlane_b32 s4, v228, 4
	v_lshlrev_b64 v[4:5], 15, v[4:5]
	v_readlane_b32 s5, v228, 5
	v_lshlrev_b32_e32 v2, 2, v2
	v_mov_b32_e32 v3, 0
	v_lshl_add_u64 v[4:5], s[4:5], 0, v[4:5]
	v_lshl_add_u64 v[2:3], v[4:5], 0, v[2:3]
	v_add_co_u32_e32 v2, vcc, 0x8280000, v2
	s_nop 1
	v_addc_co_u32_e32 v3, vcc, 0, v3, vcc
	global_store_dword v[2:3], v1, off

.LBB0_2269:
	v_mov_b32_e32 v138, v0
	s_cmp_lg_u32 s4, s37
	v_readfirstlane_b32 s84, v138
	s_mov_b64 s[6:7], -1
	s_cbranch_scc0 .LBB0_2283
	s_cmp_gt_u32 s4, s37
	s_cselect_b64 s[6:7], -1, 0
	v_cndmask_b32_e64 v1, 0, 1, s[6:7]
	s_mov_b64 s[68:69], s[66:67]
	v_readfirstlane_b32 s5, v1
	s_cmp_eq_u32 s4, s5
	s_cselect_b32 s5, 0, 0x100
	s_add_i32 s5, s5, s40
	s_cmpk_lt_i32 s5, 0x100
	v_readlane_b32 s5, v228, 29
	s_cselect_b32 s65, s41, s5
	s_mov_b32 s5, s36
	v_mov_b32_e32 v91, v0
	s_lshl_b32 s52, s65, 6
	v_readfirstlane_b32 s6, v91
	s_ashr_i32 s28, s6, 6
	s_lshl_b32 s70, s28, 3
	s_add_i32 s6, s70, s52
	v_bfe_u32 v100, v91, 2, 3
	v_or_b32_e32 v96, s6, v100
	v_ashrrev_i32_e32 v97, 31, v96
	v_and_or_b32 v1, v91, 3, s75
	v_lshl_add_u64 v[6:7], s[50:51], 0, v[96:97]
	v_mov_b64_e32 v[2:3], s[68:69]
	s_movk_i32 s8, 0x3000
	v_mad_u64_u32 v[2:3], s[6:7], v6, s8, v[2:3]
	v_mul_u32_u24_e32 v4, 3, v1
	v_mad_i32_i24 v3, v7, s8, v3
	v_lshlrev_b32_e32 v98, 2, v4
	v_lshl_add_u64 v[2:3], v[2:3], 0, v[98:99]
	v_add_co_u32_e32 v2, vcc, 0x16001000, v2
	s_lshl_b32 s29, s28, 13
	s_nop 0
	v_addc_co_u32_e32 v3, vcc, 0, v3, vcc
	global_load_dwordx3 v[2:4], v[2:3], off offset:1024
	v_and_b32_e32 v139, 63, v91
	s_add_i32 s46, s29, 0x9000
	v_and_b32_e32 v114, 31, v91
	v_lshl_or_b32 v5, v139, 2, s46
	v_or_b32_e32 v8, 0xffffffc0, v139
	s_mov_b64 s[6:7], 0
.LBB0_2271:
	v_add_u32_e32 v8, 64, v8
	s_movk_i32 s8, 0x7bf
	v_cmp_lt_u32_e32 vcc, s8, v8
	v_add_u32_e32 v9, s5, v5
	v_add_u32_e32 v5, 0x100, v5
	s_or_b64 s[6:7], vcc, s[6:7]
	ds_write_b32 v9, v99
	s_andn2_b64 exec, exec, s[6:7]
	s_cbranch_execnz .LBB0_2271
	s_or_b64 exec, exec, s[6:7]
	v_readlane_b32 s6, v228, 21
	s_add_u32 s6, s68, s6
	s_addc_u32 s7, s69, 0
	s_lshl_b32 s49, s77, 1
	s_add_u32 s6, s6, s49
	v_lshlrev_b64 v[6:7], 10, v[6:7]
	s_addc_u32 s7, s7, 0
	s_add_u32 s22, s6, 0x28800000
	v_lshl_add_u64 v[6:7], s[68:69], 0, v[6:7]
	v_lshlrev_b32_e32 v98, 7, v1
	s_addc_u32 s23, s7, 0
	v_lshl_add_u64 v[6:7], v[6:7], 0, v[98:99]
	s_mov_b64 s[6:7], 0x26800000
	v_mov_b32_e32 v5, v139
	v_lshl_add_u64 v[94:95], v[6:7], 0, s[6:7]
	s_waitcnt lgkmcnt(0)
	s_ashr_i32 s71, s70, 31
	v_ashrrev_i32_e32 v6, 5, v5
	v_lshlrev_b32_e32 v8, 3, v6
	v_ashrrev_i32_e32 v9, 31, v8
	v_lshl_add_u64 v[8:9], v[8:9], 1, v[94:95]
	global_load_dwordx4 v[34:37], v[8:9], off
	global_load_dwordx4 v[38:41], v[8:9], off offset:32
	global_load_dwordx4 v[42:45], v[8:9], off offset:64
	global_load_dwordx4 v[46:49], v[8:9], off offset:96
	v_min_i32_e32 v8, 0x1ff, v5
	v_ashrrev_i32_e32 v9, 31, v8
	v_lshlrev_b64 v[8:9], 8, v[8:9]
	v_lshl_add_u64 v[8:9], s[22:23], 0, v[8:9]
	v_lshl_add_u64 v[8:9], s[70:71], 1, v[8:9]
	s_waitcnt lgkmcnt(0)
	s_barrier
	global_load_dwordx4 v[50:53], v[8:9], off
	v_add_u32_e32 v1, 1, v1
	v_cvt_f32_ubyte0_e32 v7, v1
	s_mov_b32 s6, 0x42fc0000
	v_cmp_lt_f32_e32 vcc, s6, v7
	s_lshl_b32 s6, s28, 10
	s_add_i32 s83, s5, s6
	v_lshlrev_b32_e32 v1, 4, v5
	s_cmp_gt_u32 s65, 15
	v_cndmask_b32_e32 v8, 0, v126, vcc
	v_cndmask_b32_e32 v9, 0, v131, vcc
	v_add_u32_e32 v64, s83, v1
	s_cselect_b64 s[24:25], -1, 0
	s_cmp_lt_u32 s65, 16
	s_waitcnt vmcnt(0) lgkmcnt(0)
	ds_write_b128 v64, v[50:53]
	s_waitcnt lgkmcnt(0)
	s_barrier
	s_cbranch_scc1 .LBB0_2274
	v_min_i32_e32 v10, 0x1bf, v5
	v_ashrrev_i32_e32 v11, 31, v10
	v_lshlrev_b64 v[10:11], 8, v[10:11]
	v_lshl_add_u64 v[10:11], s[22:23], 0, v[10:11]
	v_lshl_add_u64 v[10:11], s[70:71], 1, v[10:11]
	v_add_co_u32_e32 v10, vcc, 0x4000, v10
	s_nop 1
	v_addc_co_u32_e32 v11, vcc, 0, v11, vcc
	global_load_dwordx4 v[50:53], v[10:11], off

.LBB0_2275:
	s_and_b32 s48, s31, 0x2000
	v_add_u32_e32 v58, s48, v66
	ds_read_b128 v[2:5], v58
	ds_read_b128 v[54:57], v58 offset:2048
	ds_read_b128 v[230:233], v58 offset:512
	ds_read_b128 v[234:237], v58 offset:2560
	ds_read_b128 v[238:241], v58 offset:4096
	ds_read_b128 v[242:245], v58 offset:4608
	ds_read_b128 v[246:249], v58 offset:6144
	ds_read_b128 v[250:253], v58 offset:6656
	s_waitcnt lgkmcnt(6)
	v_mfma_f32_32x32x16_bf16 v[18:33], v[2:5], v[34:37], 0
	v_mfma_f32_32x32x16_bf16 v[18:33], v[54:57], v[38:41], v[18:33]
	s_waitcnt lgkmcnt(4)
	v_mfma_f32_32x32x16_bf16 v[2:17], v[230:233], v[34:37], 0
	v_mfma_f32_32x32x16_bf16 v[2:17], v[234:237], v[38:41], v[2:17]
	s_waitcnt lgkmcnt(3)
	v_mfma_f32_32x32x16_bf16 v[18:33], v[238:241], v[42:45], v[18:33]
	s_waitcnt lgkmcnt(2)
	v_mfma_f32_32x32x16_bf16 v[2:17], v[242:245], v[42:45], v[2:17]
	s_waitcnt lgkmcnt(1)
	v_mfma_f32_32x32x16_bf16 v[18:33], v[246:249], v[46:49], v[18:33]
	s_waitcnt lgkmcnt(0)
	v_mfma_f32_32x32x16_bf16 v[2:17], v[250:253], v[46:49], v[2:17]
	v_cvt_f32_i32_e32 v54, v70
	v_cmp_lt_i32_e64 s[20:21], 62, v71
	s_cmp_eq_u64 s[20:21], exec
	v_fma_f32 v73, v90, v54, v65
	v_add_f32_e32 v56, v120, v73
	v_add_f32_e32 v57, v92, v56
	v_add_f32_e32 v74, v119, v73
	s_nop 1
	v_pk_add_f32 v[54:55], v[56:57], v[18:19]
	v_pk_add_f32 v[18:19], v[102:103], v[56:57] op_sel_hi:[1,0]
	s_nop 0
	v_pk_add_f32 v[18:19], v[18:19], v[20:21]
	v_add_f32_e32 v20, v120, v74
	v_add_f32_e32 v21, v92, v20
	v_pk_add_f32 v[62:63], v[20:21], v[2:3]
	v_pk_add_f32 v[2:3], v[102:103], v[20:21] op_sel_hi:[1,0]
	s_nop 0
	v_pk_add_f32 v[58:59], v[2:3], v[4:5]
	v_add_f32_e32 v2, v105, v73
	v_add_f32_e32 v3, v92, v2
	v_pk_add_f32 v[56:57], v[2:3], v[22:23]
	v_pk_add_f32 v[2:3], v[102:103], v[2:3] op_sel_hi:[1,0]
	s_nop 0
	v_pk_add_f32 v[20:21], v[2:3], v[24:25]
	v_add_f32_e32 v2, v105, v74
	v_add_f32_e32 v3, v92, v2
	v_pk_add_f32 v[60:61], v[2:3], v[6:7]
	v_pk_add_f32 v[2:3], v[102:103], v[2:3] op_sel_hi:[1,0]
	v_add_f32_e32 v6, v109, v74
	v_pk_add_f32 v[24:25], v[2:3], v[8:9]
	v_add_f32_e32 v2, v107, v73
	v_add_f32_e32 v3, v92, v2
	v_pk_add_f32 v[22:23], v[2:3], v[26:27]
	v_pk_add_f32 v[2:3], v[102:103], v[2:3] op_sel_hi:[1,0]
	v_add_f32_e32 v7, v92, v6
	v_pk_add_f32 v[4:5], v[2:3], v[28:29]
	v_add_f32_e32 v2, v107, v74
	v_add_f32_e32 v3, v92, v2
	v_pk_add_f32 v[26:27], v[2:3], v[10:11]
	v_pk_add_f32 v[2:3], v[102:103], v[2:3] op_sel_hi:[1,0]
	s_nop 0
	v_pk_add_f32 v[10:11], v[2:3], v[12:13]
	v_add_f32_e32 v2, v109, v73
	v_add_f32_e32 v3, v92, v2
	v_pk_add_f32 v[8:9], v[2:3], v[30:31]
	v_pk_add_f32 v[2:3], v[102:103], v[2:3] op_sel_hi:[1,0]
	v_pk_add_f32 v[12:13], v[6:7], v[14:15]
	v_pk_add_f32 v[6:7], v[102:103], v[6:7] op_sel_hi:[1,0]
	v_pk_add_f32 v[2:3], v[2:3], v[32:33]
	v_pk_add_f32 v[6:7], v[6:7], v[16:17]
	s_cbranch_scc1 .LBB0_2277
	v_add_u32_e32 v14, v69, v71
	v_cmp_gt_i32_e64 s[20:21], 0, v14
	s_or_b64 s[20:21], vcc, s[20:21]
	s_nop 0
	v_cndmask_b32_e64 v54, v54, v132, s[20:21]
	v_cmp_gt_i32_e64 s[20:21], 32, v14
	s_or_b64 s[20:21], s[6:7], s[20:21]
	s_nop 0
	v_cndmask_b32_e64 v62, v62, v132, s[20:21]
	v_cmp_gt_i32_e64 s[20:21], 1, v14
	s_or_b64 s[20:21], vcc, s[20:21]
	s_nop 0
	v_cndmask_b32_e64 v55, v55, v132, s[20:21]
	v_cmp_gt_i32_e64 s[20:21], 33, v14
	s_or_b64 s[20:21], s[6:7], s[20:21]
	s_nop 0
	v_cndmask_b32_e64 v63, v63, v132, s[20:21]
	v_cmp_gt_i32_e64 s[20:21], 2, v14
	s_or_b64 s[20:21], vcc, s[20:21]
	s_nop 0
	v_cndmask_b32_e64 v18, v18, v132, s[20:21]
	v_cmp_gt_i32_e64 s[20:21], 34, v14
	s_or_b64 s[20:21], s[6:7], s[20:21]
	s_nop 0
	v_cndmask_b32_e64 v58, v58, v132, s[20:21]
	v_cmp_gt_i32_e64 s[20:21], 3, v14
	s_or_b64 s[20:21], vcc, s[20:21]
	s_nop 0
	v_cndmask_b32_e64 v19, v19, v132, s[20:21]
	v_cmp_gt_i32_e64 s[20:21], 35, v14
	s_or_b64 s[20:21], s[6:7], s[20:21]
	s_nop 0
	v_cndmask_b32_e64 v59, v59, v132, s[20:21]
	v_cmp_gt_i32_e64 s[20:21], 8, v14
	s_or_b64 s[20:21], s[8:9], s[20:21]
	s_nop 0
	v_cndmask_b32_e64 v56, v56, v132, s[20:21]
	v_cmp_gt_i32_e64 s[20:21], 40, v14
	s_or_b64 s[20:21], s[10:11], s[20:21]
	s_nop 0
	v_cndmask_b32_e64 v60, v60, v132, s[20:21]
	v_cmp_gt_i32_e64 s[20:21], 9, v14
	s_or_b64 s[20:21], s[8:9], s[20:21]
	s_nop 0
	v_cndmask_b32_e64 v57, v57, v132, s[20:21]
	v_cmp_gt_i32_e64 s[20:21], 41, v14
	s_or_b64 s[20:21], s[10:11], s[20:21]
	s_nop 0
	v_cndmask_b32_e64 v61, v61, v132, s[20:21]
	v_cmp_gt_i32_e64 s[20:21], 10, v14
	s_or_b64 s[20:21], s[8:9], s[20:21]
	s_nop 0
	v_cndmask_b32_e64 v20, v20, v132, s[20:21]
	v_cmp_gt_i32_e64 s[20:21], 42, v14
	s_or_b64 s[20:21], s[10:11], s[20:21]
	s_nop 0
	v_cndmask_b32_e64 v24, v24, v132, s[20:21]
	v_cmp_gt_i32_e64 s[20:21], 11, v14
	s_or_b64 s[20:21], s[8:9], s[20:21]
	s_nop 0
	v_cndmask_b32_e64 v21, v21, v132, s[20:21]
	v_cmp_gt_i32_e64 s[20:21], 43, v14
	s_or_b64 s[20:21], s[10:11], s[20:21]
	s_nop 0
	v_cndmask_b32_e64 v25, v25, v132, s[20:21]
	v_cmp_gt_i32_e64 s[20:21], 16, v14
	s_or_b64 s[20:21], s[12:13], s[20:21]
	s_nop 0
	v_cndmask_b32_e64 v22, v22, v132, s[20:21]
	v_cmp_gt_i32_e64 s[20:21], 48, v14
	s_or_b64 s[20:21], s[14:15], s[20:21]
	s_nop 0
	v_cndmask_b32_e64 v26, v26, v132, s[20:21]
	v_cmp_gt_i32_e64 s[20:21], 17, v14
	s_or_b64 s[20:21], s[12:13], s[20:21]
	s_nop 0
	v_cndmask_b32_e64 v23, v23, v132, s[20:21]
	v_cmp_gt_i32_e64 s[20:21], 49, v14
	s_or_b64 s[20:21], s[14:15], s[20:21]
	s_nop 0
	v_cndmask_b32_e64 v27, v27, v132, s[20:21]
	v_cmp_gt_i32_e64 s[20:21], 18, v14
	s_or_b64 s[20:21], s[12:13], s[20:21]
	s_nop 0
	v_cndmask_b32_e64 v4, v4, v132, s[20:21]
	v_cmp_gt_i32_e64 s[20:21], 50, v14
	s_or_b64 s[20:21], s[14:15], s[20:21]
	s_nop 0
	v_cndmask_b32_e64 v10, v10, v132, s[20:21]
	v_cmp_gt_i32_e64 s[20:21], 19, v14
	s_or_b64 s[20:21], s[12:13], s[20:21]
	s_nop 0
	v_cndmask_b32_e64 v5, v5, v132, s[20:21]
	v_cmp_gt_i32_e64 s[20:21], 51, v14
	s_or_b64 s[20:21], s[14:15], s[20:21]
	s_nop 0
	v_cndmask_b32_e64 v11, v11, v132, s[20:21]
	v_cmp_gt_i32_e64 s[20:21], 24, v14
	s_or_b64 s[20:21], s[16:17], s[20:21]
	s_nop 0
	v_cndmask_b32_e64 v8, v8, v132, s[20:21]
	v_cmp_gt_i32_e64 s[20:21], 56, v14
	s_or_b64 s[20:21], s[18:19], s[20:21]
	s_nop 0
	v_cndmask_b32_e64 v12, v12, v132, s[20:21]
	v_cmp_gt_i32_e64 s[20:21], 25, v14
	s_or_b64 s[20:21], s[16:17], s[20:21]
	s_nop 0
	v_cndmask_b32_e64 v9, v9, v132, s[20:21]
	v_cmp_gt_i32_e64 s[20:21], 57, v14
	s_or_b64 s[20:21], s[18:19], s[20:21]
	s_nop 0
	v_cndmask_b32_e64 v13, v13, v132, s[20:21]
	v_cmp_gt_i32_e64 s[20:21], 26, v14
	s_or_b64 s[20:21], s[16:17], s[20:21]
	s_nop 0
	v_cndmask_b32_e64 v2, v2, v132, s[20:21]
	v_cmp_gt_i32_e64 s[20:21], 58, v14
	s_or_b64 s[20:21], s[18:19], s[20:21]
	s_nop 0
	v_cndmask_b32_e64 v6, v6, v132, s[20:21]
	v_cmp_gt_i32_e64 s[20:21], 27, v14
	s_or_b64 s[20:21], s[16:17], s[20:21]
	s_nop 0
	v_cndmask_b32_e64 v3, v3, v132, s[20:21]
	v_cmp_gt_i32_e64 s[20:21], 59, v14
	s_or_b64 s[20:21], s[18:19], s[20:21]
	s_nop 0
	v_cndmask_b32_e64 v7, v7, v132, s[20:21]

.LBB0_2279:
	s_add_i32 s20, s47, 2
	s_cmp_gt_u32 s20, s30
	s_waitcnt lgkmcnt(0)
	s_barrier
	s_cbranch_scc1 .LBB0_2281
	v_min_i32_e32 v16, 0x1ff, v68
	v_ashrrev_i32_e32 v17, 31, v16
	v_lshlrev_b64 v[16:17], 8, v[16:17]
	v_lshl_add_u64 v[16:17], s[26:27], 0, v[16:17]
	s_waitcnt vmcnt(0)
	global_load_dwordx4 v[50:53], v[16:17], off

.LBB0_2283:
	s_and_b64 vcc, exec, s[6:7]
	s_cbranch_vccz .LBB0_2895
	s_add_u32 s5, s66, s81
	s_addc_u32 s6, s67, s80
	s_add_u32 s18, s5, 0x16000000
	s_movk_i32 s5, 0x100
	v_and_b32_e32 v1, 63, v138
	s_addc_u32 s19, s6, 0
	v_cmp_gt_i32_e32 vcc, s5, v138
	s_barrier
	s_and_saveexec_b64 s[6:7], vcc
	s_cbranch_execz .LBB0_2286
	v_and_b32_e32 v2, 0xffffffc0, v138
	v_readlane_b32 s5, v228, 22
	s_nop 1
	v_add_u32_e32 v2, s5, v2
	v_or_b32_e32 v2, v2, v1
	v_ashrrev_i32_e32 v3, 31, v2
	v_lshl_add_u64 v[2:3], v[2:3], 2, s[18:19]
	global_load_dword v2, v[2:3], off
	v_lshl_add_u32 v3, v138, 2, s36
	s_waitcnt vmcnt(0) lgkmcnt(0)
	v_mul_f32_e32 v2, 0x3e000000, v2
	ds_write_b32 v3, v2

.LBB0_2289:
	v_lshl_add_u64 v[10:11], v[8:9], 0, s[10:11]
	v_add_co_u32_e32 v10, vcc, 0x6600000, v10
	v_mov_b32_e32 v3, s12
	s_nop 0
	v_addc_co_u32_e32 v11, vcc, 0, v11, vcc
	ds_read_b128 v[12:15], v3
	ds_read_b128 v[16:19], v3 offset:16
	ds_read_b128 v[20:23], v3 offset:32
	ds_read_b128 v[24:27], v3 offset:48
	ds_read_b128 v[28:31], v3 offset:256
	ds_read_b128 v[32:35], v3 offset:272
	ds_read_b128 v[36:39], v3 offset:512
	ds_read_b128 v[40:43], v3 offset:528
	ds_read_b128 v[44:47], v3 offset:768
	ds_read_b128 v[48:51], v3 offset:784
	ds_read_b128 v[52:55], v3 offset:288
	ds_read_b128 v[56:59], v3 offset:304
	ds_read_b128 v[60:63], v3 offset:544
	ds_read_b128 v[64:67], v3 offset:560
	ds_read_b128 v[68:71], v3 offset:800
	ds_read_b128 v[72:75], v3 offset:816
	global_load_dwordx4 v[76:79], v[10:11], off
	s_waitcnt vmcnt(0)
	global_load_dwordx4 v[80:83], v[10:11], off offset:16
	global_load_dwordx4 v[84:87], v[10:11], off offset:32
	global_load_dwordx4 v[88:91], v[10:11], off offset:48
	s_waitcnt lgkmcnt(0)
	v_mov_b32_e32 v10, v28
	v_mov_b32_e32 v11, v13
	v_mov_b32_e32 v28, v29
	v_mov_b32_e32 v29, v12
	v_mov_b32_e32 v12, v30
	v_mov_b32_e32 v13, v14
	v_mov_b32_e32 v14, v31
	v_mov_b32_e32 v30, v44
	v_mov_b32_e32 v31, v37
	v_mov_b32_e32 v44, v45
	v_mov_b32_e32 v45, v36
	v_mov_b32_e32 v36, v46
	v_mov_b32_e32 v37, v38
	v_mov_b32_e32 v38, v47
	v_mov_b32_e32 v46, v32
	v_mov_b32_e32 v47, v17
	v_mov_b32_e32 v32, v33
	v_mov_b32_e32 v33, v16
	v_mov_b32_e32 v16, v34
	v_mov_b32_e32 v17, v18
	v_mov_b32_e32 v18, v35
	v_mov_b32_e32 v34, v48
	v_mov_b32_e32 v35, v41
	v_mov_b32_e32 v48, v49
	v_mov_b32_e32 v49, v40
	v_mov_b32_e32 v40, v50
	v_mov_b32_e32 v41, v42
	v_mov_b32_e32 v42, v51
	v_mov_b32_e32 v50, v52
	v_mov_b32_e32 v51, v21
	v_mov_b32_e32 v52, v53
	v_mov_b32_e32 v53, v20
	v_mov_b32_e32 v20, v54
	v_mov_b32_e32 v21, v22
	v_mov_b32_e32 v22, v55
	v_mov_b32_e32 v54, v68
	v_mov_b32_e32 v55, v61
	v_mov_b32_e32 v68, v69
	v_mov_b32_e32 v69, v60
	v_mov_b32_e32 v60, v70
	v_mov_b32_e32 v61, v62
	v_mov_b32_e32 v62, v71
	v_mov_b32_e32 v70, v56
	v_mov_b32_e32 v71, v25
	v_mov_b32_e32 v56, v57
	v_mov_b32_e32 v57, v24
	v_mov_b32_e32 v24, v58
	v_mov_b32_e32 v25, v26
	v_mov_b32_e32 v26, v59
	v_mov_b32_e32 v58, v72
	v_mov_b32_e32 v59, v65
	v_mov_b32_e32 v72, v73
	v_mov_b32_e32 v73, v64
	v_mov_b32_e32 v64, v74
	s_add_i32 s12, s12, 64
	v_mov_b32_e32 v65, v66
	s_add_u32 s10, s10, 64
	v_mov_b32_e32 v66, v75
	s_addc_u32 s11, s11, 0
	s_cmpk_lg_i32 s10, 0x100
	v_pk_mul_f32 v[10:11], v[76:77], v[10:11]
	v_pk_mul_f32 v[30:31], v[76:77], v[30:31]
	s_waitcnt vmcnt(0)
	v_pk_mul_f32 v[46:47], v[80:81], v[46:47]
	v_pk_mul_f32 v[34:35], v[80:81], v[34:35]
	v_pk_fma_f32 v[10:11], v[76:77], v[28:29], v[10:11] op_sel:[1,0,0] op_sel_hi:[0,1,1]
	v_pk_fma_f32 v[28:29], v[76:77], v[44:45], v[30:31] op_sel:[1,0,0] op_sel_hi:[0,1,1]
	v_mov_b32_e32 v74, v79
	v_pk_mul_f32 v[50:51], v[84:85], v[50:51]
	v_pk_mul_f32 v[54:55], v[84:85], v[54:55]
	v_pk_fma_f32 v[30:31], v[80:81], v[32:33], v[46:47] op_sel:[1,0,0] op_sel_hi:[0,1,1]
	v_pk_fma_f32 v[32:33], v[80:81], v[48:49], v[34:35] op_sel:[1,0,0] op_sel_hi:[0,1,1]
	v_pk_fma_f32 v[10:11], v[78:79], v[12:13], v[10:11] op_sel_hi:[0,1,1]
	v_pk_fma_f32 v[12:13], v[78:79], v[36:37], v[28:29] op_sel_hi:[0,1,1]
	v_mov_b32_e32 v92, v83
	v_pk_mul_f32 v[70:71], v[88:89], v[70:71]
	v_pk_mul_f32 v[58:59], v[88:89], v[58:59]
	v_pk_fma_f32 v[34:35], v[84:85], v[52:53], v[50:51] op_sel:[1,0,0] op_sel_hi:[0,1,1]
	v_pk_fma_f32 v[44:45], v[84:85], v[68:69], v[54:55] op_sel:[1,0,0] op_sel_hi:[0,1,1]
	v_pk_fma_f32 v[16:17], v[82:83], v[16:17], v[30:31] op_sel_hi:[0,1,1]
	v_pk_fma_f32 v[28:29], v[82:83], v[40:41], v[32:33] op_sel_hi:[0,1,1]
	v_pk_fma_f32 v[10:11], v[74:75], v[14:15], v[10:11] op_sel_hi:[0,1,1]
	v_pk_fma_f32 v[12:13], v[74:75], v[38:39], v[12:13] op_sel_hi:[0,1,1]
	v_mov_b32_e32 v94, v87
	v_pk_fma_f32 v[46:47], v[88:89], v[56:57], v[70:71] op_sel:[1,0,0] op_sel_hi:[0,1,1]
	v_pk_fma_f32 v[48:49], v[88:89], v[72:73], v[58:59] op_sel:[1,0,0] op_sel_hi:[0,1,1]
	v_pk_fma_f32 v[20:21], v[86:87], v[20:21], v[34:35] op_sel_hi:[0,1,1]
	v_pk_fma_f32 v[30:31], v[86:87], v[60:61], v[44:45] op_sel_hi:[0,1,1]
	v_pk_fma_f32 v[14:15], v[92:93], v[18:19], v[16:17] op_sel_hi:[0,1,1]
	v_pk_fma_f32 v[16:17], v[92:93], v[42:43], v[28:29] op_sel_hi:[0,1,1]
	v_pk_add_f32 v[6:7], v[6:7], v[10:11]
	v_pk_add_f32 v[4:5], v[4:5], v[12:13]
	v_mov_b32_e32 v96, v91
	v_pk_fma_f32 v[24:25], v[90:91], v[24:25], v[46:47] op_sel_hi:[0,1,1]
	v_pk_fma_f32 v[32:33], v[90:91], v[64:65], v[48:49] op_sel_hi:[0,1,1]
	v_pk_fma_f32 v[18:19], v[94:95], v[22:23], v[20:21] op_sel_hi:[0,1,1]
	v_pk_fma_f32 v[20:21], v[94:95], v[62:63], v[30:31] op_sel_hi:[0,1,1]
	v_pk_add_f32 v[6:7], v[6:7], v[14:15]
	v_pk_add_f32 v[4:5], v[4:5], v[16:17]
	v_pk_fma_f32 v[22:23], v[96:97], v[26:27], v[24:25] op_sel_hi:[0,1,1]
	v_pk_fma_f32 v[24:25], v[96:97], v[66:67], v[32:33] op_sel_hi:[0,1,1]
	v_pk_add_f32 v[6:7], v[6:7], v[18:19]
	v_pk_add_f32 v[4:5], v[4:5], v[20:21]
	v_pk_add_f32 v[6:7], v[6:7], v[22:23]
	v_pk_add_f32 v[4:5], v[4:5], v[24:25]
	s_cbranch_scc1 .LBB0_2289

.LBB0_2293:
	s_add_u32 s6, s66, s86
	s_addc_u32 s7, s67, s87
	s_lshl_b32 s52, s85, 2
	s_add_u32 s8, s6, s52
	s_addc_u32 s9, s7, 0
	v_lshlrev_b32_e32 v102, 2, v1
	v_mov_b32_e32 v103, v99
	s_lshl_b32 s6, s5, 4
	v_lshl_add_u64 v[2:3], s[8:9], 0, v[102:103]
	s_mov_b64 s[8:9], 0x6600000
	v_lshl_add_u64 v[2:3], v[2:3], 0, s[8:9]
	v_mov_b32_e32 v19, 0
	s_cmp_gt_i32 s5, 7
	v_mov_b32_e32 v10, 0
	s_waitcnt lgkmcnt(0)
	s_barrier
	s_cbranch_scc1 .LBB0_2295
	s_ashr_i32 s7, s6, 31
	s_lshl_b64 s[8:9], s[6:7], 9
	v_lshl_add_u64 v[4:5], v[2:3], 0, s[8:9]
	global_load_dword v10, v[4:5], off
.LBB0_2295:
	s_or_b32 s8, s6, 1
	s_cmpk_gt_i32 s8, 0x7e
	s_cbranch_scc1 .LBB0_2297
	s_ashr_i32 s9, s8, 31
	s_lshl_b64 s[8:9], s[8:9], 9
	v_lshl_add_u64 v[4:5], v[2:3], 0, s[8:9]
	global_load_dword v19, v[4:5], off
.LBB0_2297:
	s_or_b32 s8, s6, 2
	v_mov_b32_e32 v17, 0
	s_cmpk_gt_i32 s8, 0x7e
	v_mov_b32_e32 v20, 0
	s_cbranch_scc1 .LBB0_2299
	s_ashr_i32 s9, s8, 31
	s_lshl_b64 s[8:9], s[8:9], 9
	v_lshl_add_u64 v[4:5], v[2:3], 0, s[8:9]
	global_load_dword v20, v[4:5], off
.LBB0_2299:
	s_or_b32 s8, s6, 3
	s_cmpk_gt_i32 s8, 0x7e
	s_cbranch_scc1 .LBB0_2301
	s_ashr_i32 s9, s8, 31
	s_lshl_b64 s[8:9], s[8:9], 9
	v_lshl_add_u64 v[4:5], v[2:3], 0, s[8:9]
	global_load_dword v17, v[4:5], off
.LBB0_2301:
	s_or_b32 s8, s6, 4
	v_mov_b32_e32 v15, 0
	s_cmpk_gt_i32 s8, 0x7e
	v_mov_b32_e32 v18, 0
	s_cbranch_scc1 .LBB0_2303
	s_ashr_i32 s9, s8, 31
	s_lshl_b64 s[8:9], s[8:9], 9
	v_lshl_add_u64 v[4:5], v[2:3], 0, s[8:9]
	global_load_dword v18, v[4:5], off
.LBB0_2303:
	s_or_b32 s8, s6, 5
	s_cmpk_gt_i32 s8, 0x7e
	s_cbranch_scc1 .LBB0_2305
	s_ashr_i32 s9, s8, 31
	s_lshl_b64 s[8:9], s[8:9], 9
	v_lshl_add_u64 v[4:5], v[2:3], 0, s[8:9]
	global_load_dword v15, v[4:5], off
.LBB0_2305:
	s_or_b32 s8, s6, 6
	v_mov_b32_e32 v13, 0
	s_cmpk_gt_i32 s8, 0x7e
	v_mov_b32_e32 v16, 0
	s_cbranch_scc1 .LBB0_2307
	s_ashr_i32 s9, s8, 31
	s_lshl_b64 s[8:9], s[8:9], 9
	v_lshl_add_u64 v[4:5], v[2:3], 0, s[8:9]
	global_load_dword v16, v[4:5], off
.LBB0_2307:
	s_or_b32 s8, s6, 7
	s_cmpk_gt_i32 s8, 0x7e
	s_cbranch_scc1 .LBB0_2309
	s_ashr_i32 s9, s8, 31
	s_lshl_b64 s[8:9], s[8:9], 9
	v_lshl_add_u64 v[4:5], v[2:3], 0, s[8:9]
	global_load_dword v13, v[4:5], off
.LBB0_2309:
	s_or_b32 s8, s6, 8
	v_mov_b32_e32 v11, 0
	s_cmpk_gt_i32 s8, 0x7e
	v_mov_b32_e32 v14, 0
	s_cbranch_scc1 .LBB0_2311
	s_ashr_i32 s9, s8, 31
	s_lshl_b64 s[8:9], s[8:9], 9
	v_lshl_add_u64 v[4:5], v[2:3], 0, s[8:9]
	global_load_dword v14, v[4:5], off
.LBB0_2311:
	s_or_b32 s8, s6, 9
	s_cmpk_gt_i32 s8, 0x7e
	s_cbranch_scc1 .LBB0_2313
	s_ashr_i32 s9, s8, 31
	s_lshl_b64 s[8:9], s[8:9], 9
	v_lshl_add_u64 v[4:5], v[2:3], 0, s[8:9]
	global_load_dword v11, v[4:5], off
.LBB0_2313:
	s_or_b32 s8, s6, 10
	v_mov_b32_e32 v7, 0
	s_cmpk_gt_i32 s8, 0x7e
	v_mov_b32_e32 v12, 0
	s_cbranch_scc1 .LBB0_2315
	s_ashr_i32 s9, s8, 31
	s_lshl_b64 s[8:9], s[8:9], 9
	v_lshl_add_u64 v[4:5], v[2:3], 0, s[8:9]
	global_load_dword v12, v[4:5], off
.LBB0_2315:
	s_or_b32 s8, s6, 11
	s_cmpk_gt_i32 s8, 0x7e
	s_cbranch_scc1 .LBB0_2317
	s_ashr_i32 s9, s8, 31
	s_lshl_b64 s[8:9], s[8:9], 9
	v_lshl_add_u64 v[4:5], v[2:3], 0, s[8:9]
	global_load_dword v7, v[4:5], off
.LBB0_2317:
	s_or_b32 s8, s6, 12
	v_mov_b32_e32 v4, 0
	s_cmpk_gt_i32 s8, 0x7e
	v_mov_b32_e32 v8, 0
	s_cbranch_scc1 .LBB0_2319
	s_ashr_i32 s9, s8, 31
	s_lshl_b64 s[8:9], s[8:9], 9
	v_lshl_add_u64 v[8:9], v[2:3], 0, s[8:9]
	global_load_dword v8, v[8:9], off
.LBB0_2319:
	s_or_b32 s8, s6, 13
	s_cmpk_gt_i32 s8, 0x7e
	s_cbranch_scc1 .LBB0_2321
	s_ashr_i32 s9, s8, 31
	s_lshl_b64 s[8:9], s[8:9], 9
	v_lshl_add_u64 v[4:5], v[2:3], 0, s[8:9]
	global_load_dword v4, v[4:5], off
.LBB0_2321:
	s_or_b32 s8, s6, 14
	v_mov_b32_e32 v5, 0
	s_cmpk_gt_i32 s8, 0x7e
	v_mov_b32_e32 v6, 0
	s_cbranch_scc1 .LBB0_2323
	s_ashr_i32 s9, s8, 31
	s_lshl_b64 s[8:9], s[8:9], 9
	v_lshl_add_u64 v[22:23], v[2:3], 0, s[8:9]
	global_load_dword v6, v[22:23], off
.LBB0_2323:
	s_or_b32 s6, s6, 15
	s_cmpk_gt_i32 s6, 0x7e
	s_cbranch_scc1 .LBB0_2325
	s_ashr_i32 s7, s6, 31
	s_lshl_b64 s[6:7], s[6:7], 9
	v_lshl_add_u64 v[2:3], v[2:3], 0, s[6:7]
	global_load_dword v5, v[2:3], off

.LBB0_2725:
	v_mov_b64_e32 v[4:5], s[0:1]
	s_waitcnt lgkmcnt(0)
	s_barrier
	global_load_dwordx2 v[2:3], v[4:5], off offset:40 sc0 sc1
	s_waitcnt vmcnt(0)
	global_load_dwordx2 v[10:11], v[4:5], off offset:48 sc0 sc1
	s_waitcnt vmcnt(0)
	global_load_dwordx2 v[4:5], v[4:5], off offset:64 sc0 sc1
	s_waitcnt vmcnt(0)
	s_lshl_b32 s6, s5, 2
	s_add_i32 s6, s36, s6
	v_mov_b32_e32 v6, s6
	v_add_u32_e32 v6, 0xc00, v6
	ds_read2_b32 v[6:7], v6 offset1:8
	s_mov_b64 s[8:9], -1
	s_waitcnt lgkmcnt(0)
	v_cmp_lt_i32_e32 vcc, 31, v6
	v_readfirstlane_b32 s10, v6
	v_readfirstlane_b32 s11, v7
	s_cbranch_vccz .LBB0_2745
	s_add_u32 s6, s18, 0xc00
	s_addc_u32 s7, s19, 0
	v_lshl_add_u64 v[4:5], s[58:59], 2, v[4:5]
	v_mov_b64_e32 v[6:7], s[6:7]
	s_cbranch_execz .LBB0_2746

.LBB0_2731:
	s_or_b64 exec, exec, s[6:7]
	v_mov_b32_e32 v2, v139
	s_add_u32 s6, s68, s82
	v_ashrrev_i32_e32 v3, 5, v2
	v_lshlrev_b32_e32 v6, 3, v3
	v_ashrrev_i32_e32 v7, 31, v6
	s_addc_u32 s7, s69, 0
	v_lshl_add_u64 v[6:7], v[6:7], 1, v[94:95]
	s_add_u32 s6, s6, s49
	global_load_dwordx4 v[66:69], v[6:7], off
	global_load_dwordx4 v[70:73], v[6:7], off offset:32
	global_load_dwordx4 v[74:77], v[6:7], off offset:64
	global_load_dwordx4 v[78:81], v[6:7], off offset:96
	v_min_i32_e32 v6, 0x1ff, v2
	s_addc_u32 s7, s7, 0
	v_ashrrev_i32_e32 v7, 31, v6
	s_add_u32 s6, s6, 0x28840000
	v_lshlrev_b64 v[6:7], 8, v[6:7]
	s_addc_u32 s7, s7, 0
	v_lshl_add_u64 v[6:7], s[22:23], 0, v[6:7]
	s_lshl_b32 s8, s28, 4
	v_lshlrev_b32_e32 v4, 3, v2
	v_lshl_add_u64 v[8:9], s[70:71], 1, v[6:7]
	s_and_b32 s48, s8, 48
	v_ashrrev_i32_e32 v6, 2, v2
	v_and_b32_e32 v5, 24, v4
	v_add_u32_e32 v4, s48, v6
	v_min_i32_e32 v10, 0x1ff, v4
	v_ashrrev_i32_e32 v11, 31, v10
	v_lshlrev_b64 v[10:11], 8, v[10:11]
	s_and_b32 s72, s70, 0xffffffe0
	v_lshl_add_u64 v[10:11], s[6:7], 0, v[10:11]
	s_ashr_i32 s73, s72, 31
	v_lshl_add_u64 v[10:11], s[72:73], 1, v[10:11]
	v_lshlrev_b32_e32 v98, 1, v5
	s_waitcnt lgkmcnt(0)
	s_barrier
	v_lshl_add_u64 v[10:11], v[10:11], 0, v[98:99]
	global_load_dwordx4 v[82:85], v[8:9], off
	global_load_dwordx4 v[86:89], v[10:11], off
	v_lshl_add_u32 v124, v2, 4, s83
	s_andn2_b64 vcc, exec, s[24:25]
	s_waitcnt vmcnt(0) lgkmcnt(0)
	ds_write_b128 v124, v[82:85]
	ds_write_b128 v124, v[86:89] offset:16384
	s_waitcnt lgkmcnt(0)
	s_barrier
	s_cbranch_vccnz .LBB0_2733
	v_min_i32_e32 v8, 0x1bf, v2
	v_ashrrev_i32_e32 v9, 31, v8
	v_add3_u32 v6, v6, s48, 64
	v_lshlrev_b64 v[8:9], 8, v[8:9]
	v_min_i32_e32 v6, 0x1ff, v6
	v_lshl_add_u64 v[8:9], s[22:23], 0, v[8:9]
	v_ashrrev_i32_e32 v7, 31, v6
	v_lshl_add_u64 v[8:9], s[70:71], 1, v[8:9]
	v_lshlrev_b64 v[6:7], 8, v[6:7]
	v_add_co_u32_e32 v8, vcc, 0x4000, v8
	v_lshl_add_u64 v[6:7], s[6:7], 0, v[6:7]
	s_nop 0
	v_addc_co_u32_e32 v9, vcc, 0, v9, vcc
	v_lshl_add_u64 v[6:7], s[72:73], 1, v[6:7]
	v_lshl_add_u64 v[6:7], v[6:7], 0, v[98:99]
	global_load_dwordx4 v[82:85], v[8:9], off
	global_load_dwordx4 v[86:89], v[6:7], off

.LBB0_2735:
	s_and_b32 s47, s31, 0x2000
	v_add_u32_e32 v112, s47, v142
	ds_read_b128 v[34:37], v112
	ds_read_b128 v[146:149], v112 offset:2048
	ds_read_b128 v[230:233], v112 offset:512
	ds_read_b128 v[234:237], v112 offset:2560
	ds_read_b128 v[238:241], v112 offset:4096
	ds_read_b128 v[242:245], v112 offset:4608
	ds_read_b128 v[246:249], v112 offset:6144
	ds_read_b128 v[250:253], v112 offset:6656
	s_waitcnt lgkmcnt(6)
	v_mfma_f32_32x32x16_bf16 v[50:65], v[34:37], v[66:69], 0
	v_mfma_f32_32x32x16_bf16 v[50:65], v[146:149], v[70:73], v[50:65]
	s_waitcnt lgkmcnt(4)
	v_mfma_f32_32x32x16_bf16 v[34:49], v[230:233], v[66:69], 0
	v_mfma_f32_32x32x16_bf16 v[34:49], v[234:237], v[70:73], v[34:49]
	s_waitcnt lgkmcnt(3)
	v_mfma_f32_32x32x16_bf16 v[50:65], v[238:241], v[74:77], v[50:65]
	s_waitcnt lgkmcnt(2)
	v_mfma_f32_32x32x16_bf16 v[34:49], v[242:245], v[74:77], v[34:49]
	s_waitcnt lgkmcnt(1)
	v_mfma_f32_32x32x16_bf16 v[50:65], v[246:249], v[78:81], v[50:65]
	s_waitcnt lgkmcnt(0)
	v_mfma_f32_32x32x16_bf16 v[34:49], v[250:253], v[78:81], v[34:49]
	v_cvt_f32_i32_e32 v112, v121
	v_cmp_lt_i32_e64 s[22:23], 62, v1
	s_cmp_eq_u64 s[22:23], exec
	v_fma_f32 v154, v90, v112, v141
	v_add_f32_e32 v146, v120, v154
	v_add_f32_e32 v148, v105, v154
	v_add_f32_e32 v147, v92, v146
	v_add_f32_e32 v149, v92, v148
	s_nop 0
	v_pk_add_f32 v[112:113], v[146:147], v[50:51]
	v_pk_add_f32 v[50:51], v[102:103], v[146:147] op_sel_hi:[1,0]
	v_add_f32_e32 v152, v107, v154
	v_pk_add_f32 v[50:51], v[50:51], v[52:53]
	v_pk_add_f32 v[52:53], v[148:149], v[54:55]
	v_pk_add_f32 v[54:55], v[102:103], v[148:149] op_sel_hi:[1,0]
	v_add_f32_e32 v149, v119, v154
	v_pk_add_f32 v[54:55], v[54:55], v[56:57]
	v_add_f32_e32 v56, v120, v149
	v_add_f32_e32 v57, v92, v56
	v_pk_add_f32 v[34:35], v[56:57], v[34:35]
	v_add_f32_e32 v57, v102, v56
	v_add_f32_e32 v146, v57, v36
	v_mov_b32_e32 v57, v149
	v_pk_add_f32 v[150:151], v[104:105], v[56:57]
	v_mov_b32_e32 v36, v37
	v_mov_b32_e32 v37, v38
	v_pk_add_f32 v[56:57], v[92:93], v[150:151] op_sel:[0,1]
	v_mov_b32_e32 v38, v39
	v_mov_b32_e32 v39, v40
	v_add_f32_e32 v153, v92, v152
	v_mov_b32_e32 v148, v151
	v_pk_add_f32 v[36:37], v[150:151], v[36:37]
	v_pk_add_f32 v[38:39], v[56:57], v[38:39]
	v_pk_add_f32 v[56:57], v[152:153], v[58:59]
	v_pk_add_f32 v[58:59], v[102:103], v[152:153] op_sel_hi:[1,0]
	v_pk_add_f32 v[150:151], v[106:107], v[148:149]
	v_add_f32_e32 v152, v109, v154
	v_pk_add_f32 v[58:59], v[58:59], v[60:61]
	v_mov_b32_e32 v40, v41
	v_mov_b32_e32 v41, v42
	v_pk_add_f32 v[60:61], v[92:93], v[150:151] op_sel:[0,1]
	v_mov_b32_e32 v42, v43
	v_mov_b32_e32 v43, v44
	v_add_f32_e32 v153, v92, v152
	v_pk_add_f32 v[42:43], v[60:61], v[42:43]
	v_pk_add_f32 v[60:61], v[152:153], v[62:63]
	v_pk_add_f32 v[62:63], v[102:103], v[152:153] op_sel_hi:[1,0]
	v_mov_b32_e32 v148, v151
	v_pk_add_f32 v[62:63], v[62:63], v[64:65]
	v_pk_add_f32 v[64:65], v[108:109], v[148:149]
	v_mov_b32_e32 v44, v45
	v_mov_b32_e32 v45, v46
	v_pk_add_f32 v[148:149], v[92:93], v[64:65] op_sel:[0,1]
	v_mov_b32_e32 v46, v47
	v_mov_b32_e32 v47, v48
	v_add_f32_e32 v48, v104, v65
	v_pk_add_f32 v[40:41], v[150:151], v[40:41]
	v_pk_add_f32 v[44:45], v[64:65], v[44:45]
	v_pk_add_f32 v[46:47], v[148:149], v[46:47]
	v_add_f32_e32 v64, v48, v49
	s_cbranch_scc1 .LBB0_2737
	v_add_u32_e32 v48, v145, v1
	v_cmp_gt_i32_e64 s[22:23], 0, v48
	s_or_b64 s[22:23], s[6:7], s[22:23]
	v_cmp_gt_i32_e64 s[24:25], 40, v48
	v_cndmask_b32_e64 v112, v112, v132, s[22:23]
	v_cmp_gt_i32_e64 s[22:23], 32, v48
	s_or_b64 s[22:23], s[12:13], s[22:23]
	s_nop 0
	v_cndmask_b32_e64 v34, v34, v132, s[22:23]
	v_cmp_gt_i32_e64 s[22:23], 1, v48
	s_or_b64 s[22:23], s[6:7], s[22:23]
	s_nop 0
	v_cndmask_b32_e64 v113, v113, v132, s[22:23]
	v_cmp_gt_i32_e64 s[22:23], 33, v48
	s_or_b64 s[22:23], s[12:13], s[22:23]
	s_nop 0
	v_cndmask_b32_e64 v35, v35, v132, s[22:23]
	v_cmp_gt_i32_e64 s[22:23], 2, v48
	s_or_b64 s[22:23], s[6:7], s[22:23]
	s_nop 0
	v_cndmask_b32_e64 v50, v50, v132, s[22:23]
	v_cmp_gt_i32_e64 s[22:23], 34, v48
	s_or_b64 s[22:23], s[12:13], s[22:23]
	s_nop 0
	v_cndmask_b32_e64 v146, v146, v132, s[22:23]
	v_cmp_gt_i32_e64 s[22:23], 3, v48
	s_or_b64 s[22:23], s[6:7], s[22:23]
	s_nop 0
	v_cndmask_b32_e64 v51, v51, v132, s[22:23]
	v_cmp_gt_i32_e64 s[22:23], 8, v48
	s_or_b64 s[22:23], s[8:9], s[22:23]
	s_nop 0
	v_cndmask_b32_e64 v52, v52, v132, s[22:23]
	v_cmp_gt_i32_e64 s[22:23], 35, v48
	s_or_b64 s[22:23], s[12:13], s[22:23]
	s_nop 0
	v_cndmask_b32_e64 v36, v36, v132, s[22:23]
	s_or_b64 s[22:23], s[10:11], s[24:25]
	v_cndmask_b32_e64 v37, v37, v132, s[22:23]
	v_cmp_gt_i32_e64 s[22:23], 9, v48
	s_or_b64 s[22:23], s[8:9], s[22:23]
	s_nop 0
	v_cndmask_b32_e64 v53, v53, v132, s[22:23]
	v_cmp_gt_i32_e64 s[22:23], 41, v48
	s_or_b64 s[22:23], s[10:11], s[22:23]
	s_nop 0
	v_cndmask_b32_e64 v38, v38, v132, s[22:23]
	v_cmp_gt_i32_e64 s[22:23], 10, v48
	s_or_b64 s[22:23], s[8:9], s[22:23]
	s_nop 0
	v_cndmask_b32_e64 v54, v54, v132, s[22:23]
	v_cmp_gt_i32_e64 s[22:23], 42, v48
	s_or_b64 s[22:23], s[10:11], s[22:23]
	s_nop 0
	v_cndmask_b32_e64 v39, v39, v132, s[22:23]
	v_cmp_gt_i32_e64 s[22:23], 11, v48
	s_or_b64 s[22:23], s[8:9], s[22:23]
	s_nop 0
	v_cndmask_b32_e64 v55, v55, v132, s[22:23]
	v_cmp_gt_i32_e64 s[22:23], 43, v48
	s_or_b64 s[22:23], s[10:11], s[22:23]
	s_nop 0
	v_cndmask_b32_e64 v40, v40, v132, s[22:23]
	v_cmp_gt_i32_e64 s[22:23], 16, v48
	s_or_b64 s[22:23], s[14:15], s[22:23]
	s_nop 0
	v_cndmask_b32_e64 v56, v56, v132, s[22:23]
	v_cmp_gt_i32_e64 s[22:23], 48, v48
	s_or_b64 s[22:23], s[16:17], s[22:23]
	s_nop 0
	v_cndmask_b32_e64 v41, v41, v132, s[22:23]
	v_cmp_gt_i32_e64 s[22:23], 17, v48
	s_or_b64 s[22:23], s[14:15], s[22:23]
	s_nop 0
	v_cndmask_b32_e64 v57, v57, v132, s[22:23]
	v_cmp_gt_i32_e64 s[22:23], 49, v48
	s_or_b64 s[22:23], s[16:17], s[22:23]
	s_nop 0
	v_cndmask_b32_e64 v42, v42, v132, s[22:23]
	v_cmp_gt_i32_e64 s[22:23], 18, v48
	s_or_b64 s[22:23], s[14:15], s[22:23]
	s_nop 0
	v_cndmask_b32_e64 v58, v58, v132, s[22:23]
	v_cmp_gt_i32_e64 s[22:23], 50, v48
	s_or_b64 s[22:23], s[16:17], s[22:23]
	s_nop 0
	v_cndmask_b32_e64 v43, v43, v132, s[22:23]
	v_cmp_gt_i32_e64 s[22:23], 19, v48
	s_or_b64 s[22:23], s[14:15], s[22:23]
	s_nop 0
	v_cndmask_b32_e64 v59, v59, v132, s[22:23]
	v_cmp_gt_i32_e64 s[22:23], 51, v48
	s_or_b64 s[22:23], s[16:17], s[22:23]
	s_nop 0
	v_cndmask_b32_e64 v44, v44, v132, s[22:23]
	v_cmp_gt_i32_e64 s[22:23], 24, v48
	s_or_b64 s[22:23], s[18:19], s[22:23]
	s_nop 0
	v_cndmask_b32_e64 v60, v60, v132, s[22:23]
	v_cmp_gt_i32_e64 s[22:23], 56, v48
	s_or_b64 s[22:23], s[20:21], s[22:23]
	s_nop 0
	v_cndmask_b32_e64 v45, v45, v132, s[22:23]
	v_cmp_gt_i32_e64 s[22:23], 25, v48
	s_or_b64 s[22:23], s[18:19], s[22:23]
	s_nop 0
	v_cndmask_b32_e64 v61, v61, v132, s[22:23]
	v_cmp_gt_i32_e64 s[22:23], 57, v48
	s_or_b64 s[22:23], s[20:21], s[22:23]
	s_nop 0
	v_cndmask_b32_e64 v46, v46, v132, s[22:23]
	v_cmp_gt_i32_e64 s[22:23], 26, v48
	s_or_b64 s[22:23], s[18:19], s[22:23]
	s_nop 0
	v_cndmask_b32_e64 v62, v62, v132, s[22:23]
	v_cmp_gt_i32_e64 s[22:23], 58, v48
	s_or_b64 s[22:23], s[20:21], s[22:23]
	s_nop 0
	v_cndmask_b32_e64 v47, v47, v132, s[22:23]
	v_cmp_gt_i32_e64 s[22:23], 27, v48
	s_or_b64 s[22:23], s[18:19], s[22:23]
	s_nop 0
	v_cndmask_b32_e64 v63, v63, v132, s[22:23]
	v_cmp_gt_i32_e64 s[22:23], 59, v48
	s_or_b64 s[22:23], s[20:21], s[22:23]
	s_nop 0
	v_cndmask_b32_e64 v64, v64, v132, s[22:23]

.LBB0_2743:
	s_add_i32 s22, s46, 2
	s_cmp_gt_u32 s22, s30
	s_waitcnt lgkmcnt(0)
	s_barrier
	s_cbranch_scc1 .LBB0_2734
	v_min_i32_e32 v34, 0x1ff, v143
	v_ashrrev_i32_e32 v35, 31, v34
	v_min_i32_e32 v36, 0x1ff, v98
	v_lshlrev_b64 v[34:35], 8, v[34:35]
	v_ashrrev_i32_e32 v37, 31, v36
	v_lshl_add_u64 v[34:35], s[26:27], 0, v[34:35]
	v_lshlrev_b64 v[36:37], 8, v[36:37]
	v_lshl_add_u64 v[36:37], v[110:111], 0, v[36:37]
	s_waitcnt vmcnt(0)
	global_load_dwordx4 v[82:85], v[34:35], off
	global_load_dwordx4 v[86:89], v[36:37], off
	s_branch .LBB0_2734

.LBB0_2749:
	s_or_b32 s6, s14, 1
	s_ashr_i32 s7, s6, 31
	s_lshl_b32 s26, s10, 6
	s_lshl_b32 s27, s11, 6
	s_add_i32 s28, s14, 0x601
	s_lshl_b64 s[6:7], s[6:7], 10
	v_lshrrev_b32_e32 v100, 4, v1
	s_add_u32 s8, s18, s52
	v_or_b32_e32 v14, s26, v100
	s_addc_u32 s9, s19, 0
	v_or_b32_e32 v17, 4, v14
	s_add_u32 s29, s8, 0xc00
	v_subrev_u32_e32 v12, s26, v17
	v_lshl_add_u64 v[104:105], v[6:7], 0, s[52:53]
	s_addc_u32 s30, s9, 0
	v_lshlrev_b32_e32 v98, 10, v100
	v_ashrrev_i32_e32 v13, 31, v12
	v_lshl_add_u64 v[2:3], v[104:105], 0, v[98:99]
	v_mov_b32_e32 v15, s30
	v_cmp_gt_i32_e32 vcc, s44, v14
	v_mov_b32_e32 v16, s29
	v_lshlrev_b64 v[12:13], 10, v[12:13]
	v_and_b32_e32 v50, 15, v138
	v_cndmask_b32_e32 v3, v15, v3, vcc
	v_cndmask_b32_e32 v2, v16, v2, vcc
	v_lshl_add_u64 v[12:13], v[104:105], 0, v[12:13]
	v_cmp_gt_i32_e32 vcc, s44, v17
	v_lshlrev_b32_e32 v98, 4, v50
	v_lshl_add_u64 v[6:7], v[2:3], 0, v[98:99]
	v_cndmask_b32_e32 v13, v15, v13, vcc
	v_cndmask_b32_e32 v12, v16, v12, vcc
	v_lshl_add_u64 v[12:13], v[12:13], 0, v[98:99]
	v_or_b32_e32 v17, 8, v14
	global_load_dwordx4 v[2:5], v[6:7], off nt
	s_nop 0
	global_load_dwordx4 v[6:9], v[6:7], off offset:512 nt
	s_nop 0
	global_load_dwordx4 v[26:29], v[12:13], off nt
	global_load_dwordx4 v[30:33], v[12:13], off offset:512 nt
	v_subrev_u32_e32 v12, s26, v17
	v_ashrrev_i32_e32 v13, 31, v12
	v_lshlrev_b64 v[12:13], 10, v[12:13]
	v_lshl_add_u64 v[12:13], v[104:105], 0, v[12:13]
	v_cmp_gt_i32_e32 vcc, s44, v17
	v_or_b32_e32 v14, 12, v14
	v_lshl_add_u64 v[108:109], v[42:43], 0, s[52:53]
	v_cndmask_b32_e32 v13, v15, v13, vcc
	v_cndmask_b32_e32 v12, v16, v12, vcc
	v_lshl_add_u64 v[12:13], v[12:13], 0, v[98:99]
	global_load_dwordx4 v[34:37], v[12:13], off nt
	global_load_dwordx4 v[38:41], v[12:13], off offset:512 nt
	v_subrev_u32_e32 v12, s26, v14
	v_ashrrev_i32_e32 v13, 31, v12
	v_lshlrev_b64 v[12:13], 10, v[12:13]
	v_lshl_add_u64 v[12:13], v[104:105], 0, v[12:13]
	v_cmp_gt_i32_e32 vcc, s44, v14
	v_and_b32_e32 v43, 64, v166
	v_xor_b32_e32 v42, 1, v166
	v_cndmask_b32_e32 v13, v15, v13, vcc
	v_cndmask_b32_e32 v12, v16, v12, vcc
	v_lshl_add_u64 v[12:13], v[12:13], 0, v[98:99]
	global_load_dwordx4 v[46:49], v[12:13], off nt
	global_load_dwordx4 v[54:57], v[12:13], off offset:512 nt
	v_add_u32_e32 v43, 64, v43
	v_cmp_lt_i32_e32 vcc, v42, v43
	v_lshl_add_u64 v[10:11], v[10:11], 0, s[56:57]
	v_lshl_add_u64 v[10:11], v[10:11], 0, s[6:7]
	v_cndmask_b32_e32 v42, v166, v42, vcc
	v_lshlrev_b32_e32 v138, 2, v42
	v_xor_b32_e32 v42, 2, v166
	v_cmp_lt_i32_e32 vcc, v42, v43
	v_lshlrev_b32_e32 v103, 4, v1
	v_lshl_add_u64 v[106:107], v[10:11], 0, s[52:53]
	v_cndmask_b32_e32 v42, v166, v42, vcc
	v_lshlrev_b32_e32 v139, 2, v42
	v_xor_b32_e32 v42, 4, v166
	v_cmp_lt_i32_e32 vcc, v42, v43
	v_and_b32_e32 v10, 0xf0, v103
	v_add_u32_e32 v22, s36, v10
	v_cndmask_b32_e32 v42, v166, v42, vcc
	v_lshlrev_b32_e32 v140, 2, v42
	v_xor_b32_e32 v42, 8, v166
	v_cmp_lt_i32_e32 vcc, v42, v43
	ds_read_b128 v[10:13], v22
	ds_read_b128 v[14:17], v22 offset:256
	ds_read_b128 v[18:21], v22 offset:512
	ds_read_b128 v[22:25], v22 offset:768
	v_cndmask_b32_e32 v42, v166, v42, vcc
	v_lshlrev_b32_e32 v141, 2, v42
	v_xor_b32_e32 v42, 16, v166
	v_cmp_lt_i32_e32 vcc, v42, v43
	v_mov_b32_e32 v44, v99
	v_mov_b32_e32 v45, v99
	v_cndmask_b32_e32 v42, v166, v42, vcc
	v_lshlrev_b32_e32 v142, 2, v42
	v_xor_b32_e32 v42, 32, v166
	v_cmp_lt_i32_e32 vcc, v42, v43
	s_add_u32 s31, s8, 0x1000
	v_mov_b32_e32 v43, v99
	v_cndmask_b32_e32 v42, v166, v42, vcc
	v_lshlrev_b32_e32 v143, 2, v42
	v_mov_b32_e32 v42, v99
	v_mov_b32_e32 v111, 0xff800000
	v_mov_b32_e32 v110, 0
	v_lshlrev_b32_e32 v98, 4, v50
	v_mov_b64_e32 v[52:53], v[44:45]
	v_mov_b64_e32 v[60:61], v[44:45]
	v_mov_b64_e32 v[64:65], v[44:45]
	s_addc_u32 s48, s9, 0
	s_mov_b32 s52, 0
	s_mov_b32 s49, 32
	v_cmp_eq_u32_e64 s[6:7], 0, v1
	v_cmp_gt_u32_e64 s[8:9], 16, v1
	v_mov_b64_e32 v[50:51], v[42:43]
	v_mov_b64_e32 v[58:59], v[42:43]
	v_mov_b64_e32 v[62:63], v[42:43]
	v_mov_b32_e32 v114, v110
	v_mov_b32_e32 v115, v111
	v_mov_b32_e32 v116, v110
	v_mov_b32_e32 v117, v111
	v_mov_b32_e32 v112, v110
	v_mov_b32_e32 v113, v111
	s_branch .LBB0_2752

.LBB0_2752:
	s_lshr_b32 s10, s52, 2
	s_cmp_lt_u32 s52, 4
	s_cselect_b64 vcc, -1, 0
	s_cmp_eq_u32 s10, 2
	s_cselect_b32 s12, s31, s29
	s_cselect_b32 s13, s48, s30
	s_cmp_eq_u32 s10, 1
	s_cselect_b64 s[10:11], -1, 0
	v_cndmask_b32_e64 v66, v106, v108, s[10:11]
	v_cndmask_b32_e64 v67, v107, v109, s[10:11]
	s_and_b64 s[10:11], s[10:11], exec
	s_cselect_b32 s14, s27, s28
	s_and_b64 s[10:11], vcc, exec
	s_cselect_b32 s14, s26, s14
	s_sub_i32 s10, s49, 32
	s_and_b32 s15, s10, 32
	s_or_b32 s10, s15, s14
	v_add_u32_e32 v80, s10, v100
	v_add_u32_e32 v144, 16, v80
	v_cndmask_b32_e32 v78, v66, v104, vcc
	v_subrev_u32_e32 v66, s14, v144
	v_cndmask_b32_e32 v79, v67, v105, vcc
	v_ashrrev_i32_e32 v67, 31, v66
	v_lshlrev_b64 v[66:67], 10, v[66:67]
	v_lshl_add_u64 v[66:67], v[78:79], 0, v[66:67]
	v_mov_b32_e32 v82, s13
	v_cmp_gt_i32_e64 s[10:11], s44, v144
	v_mov_b32_e32 v83, s12
	v_add_u32_e32 v147, 20, v80
	v_cndmask_b32_e64 v67, v82, v67, s[10:11]
	v_cndmask_b32_e64 v66, v83, v66, s[10:11]
	v_lshl_add_u64 v[66:67], v[66:67], 0, v[98:99]
	v_add_u32_e32 v146, 24, v80
	v_add_u32_e32 v145, 28, v80
	global_load_dwordx4 v[94:97], v[66:67], off nt
	global_load_dwordx4 v[74:77], v[66:67], off offset:512 nt
	v_subrev_u32_e32 v66, s14, v147
	v_subrev_u32_e32 v70, s14, v146
	v_subrev_u32_e32 v80, s14, v145
	v_ashrrev_i32_e32 v67, 31, v66
	v_ashrrev_i32_e32 v71, 31, v70
	v_ashrrev_i32_e32 v81, 31, v80
	v_lshlrev_b64 v[66:67], 10, v[66:67]
	v_lshlrev_b64 v[70:71], 10, v[70:71]
	v_lshlrev_b64 v[80:81], 10, v[80:81]
	v_lshl_add_u64 v[66:67], v[78:79], 0, v[66:67]
	v_lshl_add_u64 v[70:71], v[78:79], 0, v[70:71]
	v_lshl_add_u64 v[78:79], v[78:79], 0, v[80:81]
	s_waitcnt vmcnt(0) lgkmcnt(0)
	v_mul_f32_e32 v80, v11, v3
	v_fmac_f32_e32 v80, v10, v2
	v_fmac_f32_e32 v80, v12, v4
	v_fmac_f32_e32 v80, v13, v5
	ds_bpermute_b32 v81, v138, v80
	v_cmp_gt_i32_e64 s[10:11], s44, v147
	v_mul_f32_e32 v148, v11, v27
	v_fmac_f32_e32 v148, v10, v26
	v_cndmask_b32_e64 v67, v82, v67, s[10:11]
	s_waitcnt lgkmcnt(0)
	v_add_f32_e32 v80, v80, v81
	v_cndmask_b32_e64 v66, v83, v66, s[10:11]
	v_cmp_gt_i32_e64 s[10:11], s44, v146
	ds_bpermute_b32 v81, v139, v80
	v_mul_f32_e32 v125, v23, v3
	v_cndmask_b32_e64 v71, v82, v71, s[10:11]
	v_cndmask_b32_e64 v70, v83, v70, s[10:11]
	v_cmp_gt_i32_e64 s[10:11], s44, v145
	s_waitcnt lgkmcnt(0)
	v_add_f32_e32 v80, v80, v81
	ds_bpermute_b32 v81, v140, v80
	v_cndmask_b32_e64 v79, v82, v79, s[10:11]
	v_mul_f32_e32 v82, v15, v3
	v_fmac_f32_e32 v82, v14, v2
	v_fmac_f32_e32 v82, v16, v4
	v_fmac_f32_e32 v82, v17, v5
	v_cndmask_b32_e64 v78, v83, v78, s[10:11]
	ds_bpermute_b32 v83, v138, v82
	s_and_b32 s10, s52, 12
	s_waitcnt lgkmcnt(1)
	v_add_f32_e32 v118, v80, v81
	s_cmp_eq_u32 s10, 4
	ds_bpermute_b32 v119, v141, v118
	s_waitcnt lgkmcnt(1)
	v_add_f32_e32 v120, v82, v83
	ds_bpermute_b32 v121, v139, v120
	s_cselect_b32 s12, s27, s28
	s_and_b64 s[10:11], vcc, exec
	s_cselect_b32 s10, s26, s12
	s_or_b32 s10, s10, s15
	v_add_u32_e32 v156, s10, v100
	v_sub_u32_e32 v84, 0x800, v156
	s_waitcnt lgkmcnt(1)
	v_add_f32_e32 v118, v118, v119
	s_waitcnt lgkmcnt(0)
	v_add_f32_e32 v119, v120, v121
	v_cvt_f32_u32_e32 v124, v84
	ds_bpermute_b32 v120, v140, v119
	v_cmp_gt_i32_e32 vcc, s45, v156
	v_fmac_f32_e32 v125, v22, v2
	v_fma_f32 v118, -v127, v124, v118
	v_cndmask_b32_e32 v169, v135, v118, vcc
	s_waitcnt lgkmcnt(0)
	v_add_f32_e32 v120, v119, v120
	v_pk_mul_f32 v[118:119], v[12:13], v[28:29]
	v_fmac_f32_e32 v125, v24, v4
	v_add_f32_e32 v118, v118, v148
	v_add_f32_e32 v118, v119, v118
	ds_bpermute_b32 v119, v138, v118
	v_fmac_f32_e32 v125, v25, v5
	ds_bpermute_b32 v148, v138, v125
	v_mul_f32_e32 v150, v15, v27
	v_fmac_f32_e32 v150, v14, v26
	s_waitcnt lgkmcnt(1)
	v_add_f32_e32 v118, v118, v119
	ds_bpermute_b32 v119, v139, v118
	v_fmac_f32_e32 v150, v16, v28
	s_waitcnt lgkmcnt(1)
	v_add_f32_e32 v125, v125, v148
	v_fmac_f32_e32 v150, v17, v29
	ds_bpermute_b32 v148, v139, v125
	s_waitcnt lgkmcnt(1)
	v_add_f32_e32 v118, v118, v119
	ds_bpermute_b32 v119, v140, v118
	ds_bpermute_b32 v151, v138, v150
	s_movk_i32 s10, 0x7fd
	s_waitcnt lgkmcnt(2)
	v_add_f32_e32 v148, v125, v148
	v_sub_u32_e32 v125, 0x7fc, v156
	s_waitcnt lgkmcnt(1)
	v_add_f32_e32 v118, v118, v119
	ds_bpermute_b32 v119, v141, v118
	v_cvt_f32_u32_e32 v125, v125
	v_cmp_gt_i32_e64 s[10:11], s10, v156
	v_mul_f32_e32 v154, v11, v35
	v_fmac_f32_e32 v154, v10, v34
	s_waitcnt lgkmcnt(0)
	v_add_f32_e32 v118, v118, v119
	v_add_f32_e32 v119, v150, v151
	ds_bpermute_b32 v150, v139, v119
	v_mul_f32_e32 v151, v19, v27
	v_fma_f32 v118, -v127, v125, v118
	v_fmac_f32_e32 v151, v18, v26
	v_fmac_f32_e32 v151, v20, v28
	v_cndmask_b32_e64 v172, v135, v118, s[10:11]
	s_waitcnt lgkmcnt(0)
	v_add_f32_e32 v118, v119, v150
	v_fmac_f32_e32 v151, v21, v29
	ds_bpermute_b32 v119, v140, v118
	ds_bpermute_b32 v152, v138, v151
	v_lshl_add_u64 v[66:67], v[66:67], 0, v[98:99]
	v_lshl_add_u64 v[70:71], v[70:71], 0, v[98:99]
	v_lshl_add_u64 v[78:79], v[78:79], 0, v[98:99]
	s_waitcnt lgkmcnt(1)
	v_add_f32_e32 v164, v118, v119
	v_pk_mul_f32 v[118:119], v[12:13], v[36:37]
	s_waitcnt lgkmcnt(0)
	v_add_f32_e32 v150, v151, v152
	v_mul_f32_e32 v152, v23, v27
	v_add_f32_e32 v118, v118, v154
	v_fmac_f32_e32 v152, v22, v26
	v_add_f32_e32 v118, v119, v118
	v_fmac_f32_e32 v152, v24, v28
	ds_bpermute_b32 v119, v138, v118
	v_fmac_f32_e32 v152, v25, v29
	ds_bpermute_b32 v153, v138, v152
	ds_bpermute_b32 v151, v139, v150
	global_load_dwordx4 v[90:93], v[66:67], off nt
	s_nop 0
	global_load_dwordx4 v[66:69], v[66:67], off offset:512 nt
	s_waitcnt lgkmcnt(0)
	v_add_f32_e32 v118, v118, v119
	ds_bpermute_b32 v119, v139, v118
	v_add_f32_e32 v152, v152, v153
	ds_bpermute_b32 v153, v139, v152
	global_load_dwordx4 v[86:89], v[70:71], off nt
	s_nop 0
	global_load_dwordx4 v[70:73], v[70:71], off offset:512 nt
	s_nop 0
	global_load_dwordx4 v[82:85], v[78:79], off nt
	s_nop 0
	global_load_dwordx4 v[78:81], v[78:79], off offset:512 nt
	v_mul_f32_e32 v154, v15, v35
	s_waitcnt lgkmcnt(0)
	v_add_f32_e32 v118, v118, v119
	v_fmac_f32_e32 v154, v14, v34
	ds_bpermute_b32 v119, v140, v118
	v_fmac_f32_e32 v154, v16, v36
	v_add_f32_e32 v150, v150, v151
	v_add_f32_e32 v152, v152, v153
	v_fmac_f32_e32 v154, v17, v37
	ds_bpermute_b32 v151, v140, v150
	ds_bpermute_b32 v153, v140, v152
	ds_bpermute_b32 v155, v138, v154
	s_waitcnt lgkmcnt(0)
	v_add_f32_e32 v118, v118, v119
	ds_bpermute_b32 v119, v141, v118
	v_add_f32_e32 v158, v150, v151
	v_add_f32_e32 v150, v152, v153
	v_sub_u32_e32 v152, 0x7f8, v156
	v_add_f32_e32 v154, v154, v155
	v_cvt_f32_u32_e32 v152, v152
	ds_bpermute_b32 v155, v139, v154
	v_or_b32_e32 v153, 8, v156
	s_waitcnt lgkmcnt(0)
	v_add_f32_e32 v118, v118, v119
	v_fma_f32 v118, -v127, v152, v118
	v_cmp_gt_i32_e64 s[12:13], s45, v153
	v_mul_f32_e32 v153, v19, v35
	v_fmac_f32_e32 v153, v18, v34
	v_cndmask_b32_e64 v173, v135, v118, s[12:13]
	v_add_f32_e32 v118, v154, v155
	v_mul_f32_e32 v155, v23, v35
	v_fmac_f32_e32 v155, v22, v34
	v_fmac_f32_e32 v153, v20, v36
	v_fmac_f32_e32 v155, v24, v36
	v_fmac_f32_e32 v153, v21, v37
	v_fmac_f32_e32 v155, v25, v37
	ds_bpermute_b32 v154, v138, v153
	ds_bpermute_b32 v160, v138, v155
	ds_bpermute_b32 v119, v140, v118
	s_movk_i32 s14, 0x7f5
	v_cmp_gt_i32_e64 s[14:15], s14, v156
	s_waitcnt lgkmcnt(0)
	v_add_f32_e32 v153, v153, v154
	v_add_f32_e32 v160, v155, v160
	v_pk_mul_f32 v[154:155], v[10:11], v[46:47]
	v_add_f32_e32 v167, v118, v119
	v_pk_mul_f32 v[118:119], v[12:13], v[48:49]
	v_add_f32_e32 v154, v154, v155
	v_add_f32_e32 v118, v118, v154
	ds_bpermute_b32 v161, v139, v153
	ds_bpermute_b32 v162, v139, v160
	v_add_f32_e32 v118, v119, v118
	ds_bpermute_b32 v119, v138, v118
	v_mul_f32_e32 v122, v19, v3
	s_waitcnt lgkmcnt(0)
	v_add_f32_e32 v153, v153, v161
	v_add_f32_e32 v155, v160, v162
	ds_bpermute_b32 v154, v140, v153
	ds_bpermute_b32 v162, v140, v155
	v_add_f32_e32 v118, v118, v119
	ds_bpermute_b32 v119, v139, v118
	v_fmac_f32_e32 v122, v18, v2
	s_waitcnt lgkmcnt(0)
	v_add_f32_e32 v160, v153, v154
	v_add_f32_e32 v153, v155, v162
	v_mul_f32_e32 v162, v15, v47
	v_add_f32_e32 v118, v118, v119
	v_fmac_f32_e32 v162, v14, v46
	ds_bpermute_b32 v119, v140, v118
	v_fmac_f32_e32 v162, v16, v48
	v_fmac_f32_e32 v162, v17, v49
	ds_bpermute_b32 v163, v138, v162
	v_sub_u32_e32 v155, 0x7f4, v156
	s_waitcnt lgkmcnt(0)
	v_add_f32_e32 v118, v118, v119
	ds_bpermute_b32 v119, v141, v118
	v_cvt_f32_u32_e32 v155, v155
	v_add_f32_e32 v162, v162, v163
	ds_bpermute_b32 v163, v139, v162
	v_mul_f32_e32 v156, v19, v47
	s_waitcnt lgkmcnt(0)
	v_add_f32_e32 v118, v118, v119
	v_fma_f32 v118, -v127, v155, v118
	v_cndmask_b32_e64 v174, v135, v118, s[14:15]
	v_add_f32_e32 v118, v162, v163
	v_mul_f32_e32 v163, v23, v47
	v_fmac_f32_e32 v156, v18, v46
	v_fmac_f32_e32 v163, v22, v46
	v_fmac_f32_e32 v122, v20, v4
	v_fmac_f32_e32 v156, v20, v48
	v_fmac_f32_e32 v163, v24, v48
	v_fmac_f32_e32 v122, v21, v5
	v_fmac_f32_e32 v156, v21, v49
	v_fmac_f32_e32 v163, v25, v49
	ds_bpermute_b32 v123, v138, v122
	ds_bpermute_b32 v119, v140, v118
	ds_bpermute_b32 v162, v138, v156
	ds_bpermute_b32 v171, v138, v163
	v_max3_f32 v157, v169, s35, v172
	s_waitcnt lgkmcnt(0)
	v_add_f32_e32 v122, v122, v123
	v_add_f32_e32 v170, v118, v119
	v_add_f32_e32 v118, v156, v162
	v_add_f32_e32 v156, v163, v171
	ds_bpermute_b32 v123, v139, v122
	ds_bpermute_b32 v119, v139, v118
	ds_bpermute_b32 v162, v139, v156
	v_max3_f32 v157, v157, v173, v174
	ds_bpermute_b32 v163, v142, v157
	s_waitcnt lgkmcnt(0)
	v_add_f32_e32 v122, v122, v123
	v_add_f32_e32 v118, v118, v119
	v_add_f32_e32 v156, v156, v162
	ds_bpermute_b32 v123, v140, v122
	ds_bpermute_b32 v149, v140, v148
	ds_bpermute_b32 v119, v140, v118
	ds_bpermute_b32 v175, v140, v156
	v_max_f32_e32 v162, v163, v163
	v_max_f32_e32 v176, v157, v162
	ds_bpermute_b32 v177, v143, v176
	s_waitcnt lgkmcnt(0)
	v_add_f32_e32 v122, v122, v123
	v_add_f32_e32 v148, v148, v149
	v_add_f32_e32 v162, v118, v119
	v_add_f32_e32 v156, v156, v175
	ds_bpermute_b32 v121, v141, v120
	ds_bpermute_b32 v123, v141, v122
	ds_bpermute_b32 v149, v141, v148
	ds_bpermute_b32 v165, v141, v164
	ds_bpermute_b32 v159, v141, v158
	ds_bpermute_b32 v151, v141, v150
	ds_bpermute_b32 v168, v141, v167
	ds_bpermute_b32 v161, v141, v160
	ds_bpermute_b32 v154, v141, v153
	ds_bpermute_b32 v171, v141, v170
	ds_bpermute_b32 v163, v141, v162
	ds_bpermute_b32 v157, v141, v156
	v_max_f32_e32 v118, v177, v177
	v_max_f32_e32 v175, v176, v118
	v_cmp_neq_f32_e64 s[16:17], s35, v175
	v_mov_b64_e32 v[118:119], v[112:113]
	s_and_saveexec_b64 s[22:23], s[16:17]
	s_cbranch_execz .LBB0_2754
	v_max_f32_e32 v118, v175, v175
	v_max_f32_e32 v119, v113, v113
	v_max_f32_e32 v119, v119, v118
	v_sub_f32_e32 v118, v169, v119
	v_mul_f32_e32 v118, 0x3fb8aa3b, v118
	v_exp_f32_e32 v118, v118
	v_sub_f32_e32 v113, v113, v119
	v_mul_f32_e32 v113, 0x3fb8aa3b, v113
	v_add_f32_e32 v169, 0, v118
	v_pk_fma_f32 v[176:177], v[8:9], v[118:119], 0 op_sel_hi:[1,0,0]
	v_pk_fma_f32 v[178:179], v[6:7], v[118:119], 0 op_sel_hi:[1,0,0]
	v_sub_f32_e32 v118, v172, v119
	v_mul_f32_e32 v118, 0x3fb8aa3b, v118
	v_exp_f32_e32 v118, v118
	s_nop 0
	v_add_f32_e32 v169, v118, v169
	v_pk_fma_f32 v[176:177], v[32:33], v[118:119], v[176:177] op_sel_hi:[1,0,1]
	v_pk_fma_f32 v[178:179], v[30:31], v[118:119], v[178:179] op_sel_hi:[1,0,1]
	v_sub_f32_e32 v118, v173, v119
	v_mul_f32_e32 v118, 0x3fb8aa3b, v118
	v_exp_f32_e32 v118, v118
	s_nop 0
	v_add_f32_e32 v169, v118, v169
	v_pk_fma_f32 v[172:173], v[38:39], v[118:119], v[178:179] op_sel_hi:[1,0,1]
	v_pk_fma_f32 v[176:177], v[40:41], v[118:119], v[176:177] op_sel_hi:[1,0,1]
	v_sub_f32_e32 v118, v174, v119
	v_mul_f32_e32 v118, 0x3fb8aa3b, v118
	v_exp_f32_e32 v118, v118
	s_nop 0
	v_add_f32_e32 v169, v118, v169
	v_pk_fma_f32 v[174:175], v[56:57], v[118:119], v[176:177] op_sel_hi:[1,0,1]
	v_exp_f32_e32 v176, v113
	ds_bpermute_b32 v113, v142, v169
	v_pk_fma_f32 v[172:173], v[54:55], v[118:119], v[172:173] op_sel_hi:[1,0,1]
	ds_bpermute_b32 v178, v142, v174
	ds_bpermute_b32 v179, v142, v175
	s_waitcnt lgkmcnt(0)
	v_add_f32_e32 v113, v169, v113
	ds_bpermute_b32 v118, v143, v113
	v_pk_add_f32 v[174:175], v[174:175], v[178:179]
	ds_bpermute_b32 v178, v143, v174
	ds_bpermute_b32 v179, v143, v175
	s_waitcnt lgkmcnt(0)
	v_add_f32_e32 v118, v113, v118
	v_fmac_f32_e32 v118, v112, v176
	ds_bpermute_b32 v112, v142, v172
	ds_bpermute_b32 v113, v142, v173
	s_waitcnt lgkmcnt(0)
	v_pk_add_f32 v[112:113], v[172:173], v[112:113]
	ds_bpermute_b32 v172, v143, v112
	ds_bpermute_b32 v173, v143, v113
	s_waitcnt lgkmcnt(0)
	v_pk_add_f32 v[112:113], v[112:113], v[172:173]
	v_pk_add_f32 v[172:173], v[174:175], v[178:179]
	v_pk_fma_f32 v[62:63], v[62:63], v[176:177], v[112:113] op_sel_hi:[1,0,1]
	v_pk_fma_f32 v[64:65], v[64:65], v[176:177], v[172:173] op_sel_hi:[1,0,1]
	v_mov_b32_e32 v112, v118
	v_mov_b32_e32 v113, v119

.LBB0_2760:
	s_or_b64 exec, exec, s[10:11]
	s_add_i32 s54, s52, 2
	s_cmp_gt_u32 s52, 9
	s_cselect_b64 s[22:23], -1, 0
	s_and_b64 vcc, exec, s[22:23]
	s_cbranch_vccnz .LBB0_2762
	s_lshr_b32 s10, s54, 2
	s_cmp_eq_u32 s10, 2
	s_cselect_b32 s12, s31, s29
	s_cselect_b32 s13, s48, s30
	s_cmp_eq_u32 s10, 1
	s_cselect_b64 vcc, -1, 0
	s_and_b64 s[10:11], vcc, exec
	s_cselect_b32 s14, s27, s28
	s_cmp_eq_u32 s52, 0
	v_cndmask_b32_e32 v2, v106, v108, vcc
	v_cndmask_b32_e32 v3, v107, v109, vcc
	s_cselect_b64 vcc, -1, 0
	s_and_b64 s[10:11], vcc, exec
	s_cselect_b32 s10, s26, s14
	s_and_b32 s11, s49, 32
	s_or_b32 s11, s10, s11
	v_add_u32_e32 v54, s11, v100
	v_subrev_u32_e32 v48, s10, v54
	v_ashrrev_i32_e32 v49, 31, v48
	v_add_u32_e32 v26, 4, v48
	v_or_b32_e32 v36, 8, v54
	v_cndmask_b32_e32 v47, v3, v105, vcc
	v_cndmask_b32_e32 v46, v2, v104, vcc
	v_lshlrev_b64 v[2:3], 10, v[48:49]
	v_ashrrev_i32_e32 v27, 31, v26
	v_subrev_u32_e32 v34, s10, v36
	v_lshl_add_u64 v[2:3], v[46:47], 0, v[2:3]
	v_mov_b32_e32 v55, s13
	v_cmp_gt_i32_e32 vcc, s44, v54
	v_mov_b32_e32 v56, s12
	v_lshlrev_b64 v[26:27], 10, v[26:27]
	s_movk_i32 s11, 0x7fc
	v_ashrrev_i32_e32 v35, 31, v34
	v_add_u32_e32 v48, 12, v48
	v_cndmask_b32_e32 v3, v55, v3, vcc
	v_cndmask_b32_e32 v2, v56, v2, vcc
	v_lshl_add_u64 v[26:27], v[46:47], 0, v[26:27]
	v_cmp_gt_i32_e32 vcc, s11, v54
	v_lshlrev_b64 v[34:35], 10, v[34:35]
	v_ashrrev_i32_e32 v49, 31, v48
	v_cndmask_b32_e32 v27, v55, v27, vcc
	v_cndmask_b32_e32 v26, v56, v26, vcc
	v_lshl_add_u64 v[34:35], v[46:47], 0, v[34:35]
	v_cmp_gt_i32_e32 vcc, s44, v36
	v_lshlrev_b64 v[48:49], 10, v[48:49]
	s_movk_i32 s10, 0x7f4
	v_cndmask_b32_e32 v35, v55, v35, vcc
	v_cndmask_b32_e32 v34, v56, v34, vcc
	v_lshl_add_u64 v[46:47], v[46:47], 0, v[48:49]
	v_cmp_gt_i32_e32 vcc, s10, v54
	v_lshl_add_u64 v[6:7], v[2:3], 0, v[98:99]
	v_lshl_add_u64 v[30:31], v[26:27], 0, v[98:99]
	v_cndmask_b32_e32 v47, v55, v47, vcc
	v_cndmask_b32_e32 v46, v56, v46, vcc
	v_lshl_add_u64 v[38:39], v[34:35], 0, v[98:99]
	v_lshl_add_u64 v[54:55], v[46:47], 0, v[98:99]
	global_load_dwordx4 v[2:5], v[6:7], off nt
	s_nop 0
	global_load_dwordx4 v[6:9], v[6:7], off offset:512 nt
	s_nop 0
	global_load_dwordx4 v[26:29], v[30:31], off nt
	s_nop 0
	global_load_dwordx4 v[30:33], v[30:31], off offset:512 nt
	s_nop 0
	global_load_dwordx4 v[34:37], v[38:39], off nt
	s_nop 0
	global_load_dwordx4 v[38:41], v[38:39], off offset:512 nt
	s_nop 0
	global_load_dwordx4 v[46:49], v[54:55], off nt
	s_nop 0
	global_load_dwordx4 v[54:57], v[54:55], off offset:512 nt

.LBB0_2810:
	s_or_b64 exec, exec, s[8:9]
	s_lshl_b32 s30, s78, 1
	s_add_u32 s8, s68, s30
	s_addc_u32 s9, s69, 0
	v_mov_b32_e32 v2, s13
	s_add_u32 s8, s8, s49
	s_waitcnt lgkmcnt(0)
	s_barrier
	ds_read_b32 v10, v2
	v_mov_b32_e32 v2, v139
	s_addc_u32 s9, s9, 0
	s_add_u32 s31, s8, 0x27800000
	v_ashrrev_i32_e32 v4, 5, v2
	v_lshlrev_b32_e32 v6, 3, v4
	s_addc_u32 s46, s9, 0
	v_ashrrev_i32_e32 v7, 31, v6
	s_add_i32 s8, s5, 0x19404
	v_lshl_add_u64 v[6:7], v[6:7], 1, v[94:95]
	v_mov_b32_e32 v3, s8
	global_load_dwordx4 v[66:69], v[6:7], off
	global_load_dwordx4 v[70:73], v[6:7], off offset:32
	global_load_dwordx4 v[74:77], v[6:7], off offset:64
	global_load_dwordx4 v[78:81], v[6:7], off offset:96
	s_waitcnt lgkmcnt(0)
	s_barrier
	ds_read_b32 v3, v3
	v_lshlrev_b32_e32 v5, 3, v2
	v_and_b32_e32 v5, 24, v5
	v_lshlrev_b32_e32 v108, 1, v5
	v_mov_b32_e32 v109, v99
	s_waitcnt lgkmcnt(0)
	v_readfirstlane_b32 s8, v3
	s_lshl_b32 s8, s8, 6
	v_ashrrev_i32_e32 v3, 31, v2
	s_ashr_i32 s9, s8, 31
	v_lshlrev_b64 v[104:105], 9, v[2:3]
	v_ashrrev_i32_e32 v3, 2, v2
	s_lshl_b64 s[8:9], s[8:9], 9
	v_add_u32_e32 v8, s48, v3
	s_add_u32 s8, s31, s8
	v_ashrrev_i32_e32 v9, 31, v8
	s_addc_u32 s9, s46, s9
	v_lshlrev_b64 v[106:107], 9, v[8:9]
	v_lshl_add_u64 v[6:7], s[8:9], 0, v[104:105]
	v_lshl_add_u64 v[8:9], s[8:9], 0, v[106:107]
	v_lshl_add_u64 v[6:7], s[70:71], 1, v[6:7]
	v_lshl_add_u64 v[8:9], s[72:73], 1, v[8:9]
	v_lshl_add_u64 v[8:9], v[8:9], 0, v[108:109]
	s_waitcnt vmcnt(0)
	global_load_dwordx4 v[82:85], v[6:7], off
	global_load_dwordx4 v[86:89], v[8:9], off offset:256
	v_cmp_gt_i32_e32 vcc, 2, v10
	v_add_u32_e32 v159, 0x100, v34
	v_add_u32_e32 v158, 0x200, v34
	v_add_u32_e32 v157, 0x300, v34
	v_add_u32_e32 v156, 0x800, v34
	v_add_u32_e32 v155, 0x900, v34
	v_add_u32_e32 v154, 0xa00, v34
	v_add_u32_e32 v153, 0xb00, v34
	v_add_u32_e32 v152, 0x1000, v34
	v_add_u32_e32 v151, 0x1100, v34
	v_add_u32_e32 v150, 0x1200, v34
	v_add_u32_e32 v149, 0x1300, v34
	v_add_u32_e32 v148, 0x1800, v34
	v_add_u32_e32 v147, 0x1900, v34
	v_add_u32_e32 v146, 0x1a00, v34
	v_add_u32_e32 v145, 0x1b00, v34
	v_lshl_add_u32 v161, v2, 4, s83
	v_readfirstlane_b32 s47, v10
	s_and_b64 vcc, exec, vcc
	s_waitcnt vmcnt(0) lgkmcnt(0)
	ds_write_b128 v161, v[82:85]
	ds_write_b128 v161, v[86:89] offset:16384
	s_waitcnt lgkmcnt(0)
	s_barrier
	s_cbranch_vccnz .LBB0_2812
	s_add_i32 s8, s5, 0x19408
	v_mov_b32_e32 v3, s8
	ds_read_b32 v3, v3
	s_waitcnt lgkmcnt(0)
	v_readfirstlane_b32 s8, v3
	s_lshl_b32 s8, s8, 6
	s_ashr_i32 s9, s8, 31
	s_lshl_b64 s[8:9], s[8:9], 9
	s_add_u32 s8, s31, s8
	s_addc_u32 s9, s46, s9
	v_lshl_add_u64 v[6:7], s[8:9], 0, v[104:105]
	v_lshl_add_u64 v[8:9], s[8:9], 0, v[106:107]
	v_lshl_add_u64 v[6:7], s[70:71], 1, v[6:7]
	v_lshl_add_u64 v[8:9], s[72:73], 1, v[8:9]
	v_lshl_add_u64 v[8:9], v[8:9], 0, v[108:109]
	global_load_dwordx4 v[82:85], v[6:7], off
	global_load_dwordx4 v[86:89], v[8:9], off offset:256

.LBB0_2814:
	s_add_i32 s26, s28, -8
	v_mov_b32_e32 v34, s26
	ds_read_b32 v116, v34
	s_and_b32 s74, s79, 1
	s_waitcnt lgkmcnt(0)
	v_ashrrev_i32_e32 v34, 5, v116
	v_lshl_add_u32 v98, v34, 2, v165
	ds_read_b32 v34, v98
	v_lshlrev_b32_e64 v109, v116, 1
	s_waitcnt lgkmcnt(0)
	v_and_b32_e32 v34, v109, v34
	v_cmp_ne_u32_e32 vcc, 0, v34
	s_cbranch_vccz .LBB0_2823
	s_lshl_b32 s76, s74, 13
	v_add_u32_e32 v117, s76, v167
	ds_read_b128 v[34:37], v117
	ds_read_b128 v[118:121], v117 offset:2048
	ds_read_b128 v[230:233], v117 offset:512
	ds_read_b128 v[234:237], v117 offset:2560
	ds_read_b128 v[238:241], v117 offset:4096
	ds_read_b128 v[242:245], v117 offset:4608
	ds_read_b128 v[246:249], v117 offset:6144
	ds_read_b128 v[250:253], v117 offset:6656
	s_waitcnt lgkmcnt(6)
	v_mfma_f32_32x32x16_bf16 v[50:65], v[34:37], v[66:69], 0
	v_mfma_f32_32x32x16_bf16 v[50:65], v[118:121], v[70:73], v[50:65]
	s_waitcnt lgkmcnt(4)
	v_mfma_f32_32x32x16_bf16 v[34:49], v[230:233], v[66:69], 0
	v_mfma_f32_32x32x16_bf16 v[34:49], v[234:237], v[70:73], v[34:49]
	s_waitcnt lgkmcnt(3)
	v_mfma_f32_32x32x16_bf16 v[50:65], v[238:241], v[74:77], v[50:65]
	s_waitcnt lgkmcnt(2)
	v_mfma_f32_32x32x16_bf16 v[34:49], v[242:245], v[74:77], v[34:49]
	s_waitcnt lgkmcnt(1)
	v_mfma_f32_32x32x16_bf16 v[50:65], v[246:249], v[78:81], v[50:65]
	s_waitcnt lgkmcnt(0)
	v_mfma_f32_32x32x16_bf16 v[34:49], v[250:253], v[78:81], v[34:49]
	v_lshlrev_b32_e32 v116, 6, v116
	ds_read_b32 v117, v98
	v_sub_u32_e32 v98, v116, v96
	v_cvt_f32_i32_e32 v118, v98
	v_sub_u32_e32 v98, v96, v116
	v_cmp_lt_i32_e32 vcc, 62, v98
	s_waitcnt lgkmcnt(0)
	v_and_b32_e32 v109, v117, v109
	v_fma_f32 v116, v90, v118, v164
	v_sub_f32_e32 v171, v116, v168
	v_add_f32_e32 v116, v144, v171
	v_add_f32_e32 v117, v90, v116
	v_pk_add_f32 v[118:119], v[116:117], v[50:51]
	v_pk_add_f32 v[50:51], v[114:115], v[116:117] op_sel_hi:[1,0]
	v_add_f32_e32 v173, v143, v171
	v_pk_add_f32 v[116:117], v[50:51], v[52:53]
	v_add_f32_e32 v50, v111, v171
	v_add_f32_e32 v51, v90, v50
	v_add_f32_e32 v120, v144, v173
	v_pk_add_f32 v[52:53], v[50:51], v[54:55]
	v_pk_add_f32 v[50:51], v[114:115], v[50:51] op_sel_hi:[1,0]
	v_add_f32_e32 v121, v90, v120
	v_pk_add_f32 v[50:51], v[50:51], v[56:57]
	v_pk_add_f32 v[56:57], v[120:121], v[34:35]
	v_add_f32_e32 v34, v91, v120
	v_mov_b32_e32 v121, v173
	v_add_f32_e32 v54, v34, v36
	v_pk_add_f32 v[122:123], v[110:111], v[120:121]
	v_mov_b32_e32 v34, v37
	v_mov_b32_e32 v35, v38
	v_pk_add_f32 v[124:125], v[122:123], v[34:35]
	v_pk_add_f32 v[34:35], v[90:91], v[122:123] op_sel:[0,1]
	v_mov_b32_e32 v36, v39
	v_mov_b32_e32 v37, v40
	v_pk_add_f32 v[120:121], v[34:35], v[36:37]
	v_add_f32_e32 v34, v92, v171
	v_add_f32_e32 v35, v90, v34
	v_pk_add_f32 v[38:39], v[34:35], v[58:59]
	v_pk_add_f32 v[34:35], v[114:115], v[34:35] op_sel_hi:[1,0]
	v_mov_b32_e32 v172, v123
	v_pk_add_f32 v[34:35], v[34:35], v[60:61]
	v_pk_add_f32 v[60:61], v[112:113], v[172:173]
	v_mov_b32_e32 v36, v41
	v_mov_b32_e32 v37, v42
	v_pk_add_f32 v[122:123], v[60:61], v[36:37]
	v_pk_add_f32 v[36:37], v[90:91], v[60:61] op_sel:[0,1]
	v_mov_b32_e32 v40, v43
	v_mov_b32_e32 v41, v44
	v_mov_b32_e32 v172, v61
	v_cmp_ne_u32_e64 s[26:27], 0, v109
	v_pk_add_f32 v[58:59], v[36:37], v[40:41]
	v_add_f32_e32 v36, v103, v171
	v_pk_add_f32 v[42:43], v[102:103], v[172:173]
	v_mov_b32_e32 v44, v45
	v_mov_b32_e32 v45, v46
	s_and_b64 vcc, s[26:27], vcc
	v_add_f32_e32 v37, v90, v36
	v_pk_add_f32 v[60:61], v[42:43], v[44:45]
	v_pk_add_f32 v[44:45], v[90:91], v[42:43] op_sel:[0,1]
	v_add_f32_e32 v42, v110, v43
	v_cndmask_b32_e64 v43, 0, 1, vcc
	v_pk_add_f32 v[40:41], v[36:37], v[62:63]
	v_pk_add_f32 v[36:37], v[114:115], v[36:37] op_sel_hi:[1,0]
	v_mov_b32_e32 v46, v47
	v_mov_b32_e32 v47, v48
	v_cmp_ne_u32_e32 vcc, 0, v43
	v_pk_add_f32 v[36:37], v[36:37], v[64:65]
	v_pk_add_f32 v[62:63], v[44:45], v[46:47]
	s_cmp_eq_u64 vcc, exec
	v_add_f32_e32 v43, v42, v49
	s_cbranch_scc1 .LBB0_2817
	v_sub_u32_e32 v42, v98, v162
	v_cndmask_b32_e64 v64, v134, v42, s[26:27]
	v_cmp_gt_i32_e32 vcc, 0, v64
	s_or_b64 vcc, s[10:11], vcc
	v_cmp_gt_i32_e64 s[26:27], 40, v64
	v_cndmask_b32_e32 v118, v118, v132, vcc
	v_cmp_gt_i32_e32 vcc, 32, v64
	s_or_b64 vcc, s[16:17], vcc
	s_nop 0
	v_cndmask_b32_e32 v56, v56, v132, vcc
	v_cmp_gt_i32_e32 vcc, 1, v64
	s_or_b64 vcc, s[10:11], vcc
	s_nop 0
	v_cndmask_b32_e32 v119, v119, v132, vcc
	v_cmp_gt_i32_e32 vcc, 33, v64
	s_or_b64 vcc, s[16:17], vcc
	s_nop 0
	v_cndmask_b32_e32 v57, v57, v132, vcc
	v_cmp_gt_i32_e32 vcc, 2, v64
	s_or_b64 vcc, s[10:11], vcc
	s_nop 0
	v_cndmask_b32_e32 v116, v116, v132, vcc
	v_cmp_gt_i32_e32 vcc, 34, v64
	s_or_b64 vcc, s[16:17], vcc
	s_nop 0
	v_cndmask_b32_e32 v54, v54, v132, vcc
	v_cmp_gt_i32_e32 vcc, 3, v64
	s_or_b64 vcc, s[10:11], vcc
	s_nop 0
	v_cndmask_b32_e32 v117, v117, v132, vcc
	v_cmp_gt_i32_e32 vcc, 8, v64
	s_or_b64 vcc, s[12:13], vcc
	s_nop 0
	v_cndmask_b32_e32 v52, v52, v132, vcc
	v_cmp_gt_i32_e32 vcc, 35, v64
	s_or_b64 vcc, s[16:17], vcc
	s_nop 0
	v_cndmask_b32_e32 v55, v124, v132, vcc
	s_or_b64 vcc, s[14:15], s[26:27]
	v_cndmask_b32_e32 v44, v125, v132, vcc
	v_cmp_gt_i32_e32 vcc, 9, v64
	s_or_b64 vcc, s[12:13], vcc
	s_nop 0
	v_cndmask_b32_e32 v53, v53, v132, vcc
	v_cmp_gt_i32_e32 vcc, 41, v64
	s_or_b64 vcc, s[14:15], vcc
	s_nop 0
	v_cndmask_b32_e32 v45, v120, v132, vcc
	v_cmp_gt_i32_e32 vcc, 10, v64
	s_or_b64 vcc, s[12:13], vcc
	s_nop 0
	v_cndmask_b32_e32 v50, v50, v132, vcc
	v_cmp_gt_i32_e32 vcc, 42, v64
	s_or_b64 vcc, s[14:15], vcc
	s_nop 0
	v_cndmask_b32_e32 v46, v121, v132, vcc
	v_cmp_gt_i32_e32 vcc, 11, v64
	s_or_b64 vcc, s[12:13], vcc
	s_nop 0
	v_cndmask_b32_e32 v51, v51, v132, vcc
	v_cmp_gt_i32_e32 vcc, 43, v64
	s_or_b64 vcc, s[14:15], vcc
	s_nop 0
	v_cndmask_b32_e32 v47, v122, v132, vcc
	v_cmp_gt_i32_e32 vcc, 16, v64
	s_or_b64 vcc, s[18:19], vcc
	s_nop 0
	v_cndmask_b32_e32 v38, v38, v132, vcc
	v_cmp_gt_i32_e32 vcc, 48, v64
	s_or_b64 vcc, s[20:21], vcc
	s_nop 0
	v_cndmask_b32_e32 v48, v123, v132, vcc
	v_cmp_gt_i32_e32 vcc, 17, v64
	s_or_b64 vcc, s[18:19], vcc
	s_nop 0
	v_cndmask_b32_e32 v39, v39, v132, vcc
	v_cmp_gt_i32_e32 vcc, 49, v64
	s_or_b64 vcc, s[20:21], vcc
	s_nop 0
	v_cndmask_b32_e32 v49, v58, v132, vcc
	v_cmp_gt_i32_e32 vcc, 18, v64
	s_or_b64 vcc, s[18:19], vcc
	s_nop 0
	v_cndmask_b32_e32 v34, v34, v132, vcc
	v_cmp_gt_i32_e32 vcc, 50, v64
	s_or_b64 vcc, s[20:21], vcc
	s_nop 0
	v_cndmask_b32_e32 v58, v59, v132, vcc
	v_cmp_gt_i32_e32 vcc, 19, v64
	s_or_b64 vcc, s[18:19], vcc
	s_nop 0
	v_cndmask_b32_e32 v35, v35, v132, vcc
	v_cmp_gt_i32_e32 vcc, 51, v64
	s_or_b64 vcc, s[20:21], vcc
	s_nop 0
	v_cndmask_b32_e32 v59, v60, v132, vcc
	v_cmp_gt_i32_e32 vcc, 24, v64
	s_or_b64 vcc, s[22:23], vcc
	s_nop 0
	v_cndmask_b32_e32 v40, v40, v132, vcc
	v_cmp_gt_i32_e32 vcc, 56, v64
	s_or_b64 vcc, s[24:25], vcc
	s_nop 0
	v_cndmask_b32_e32 v60, v61, v132, vcc
	v_cmp_gt_i32_e32 vcc, 25, v64
	s_or_b64 vcc, s[22:23], vcc
	s_nop 0
	v_cndmask_b32_e32 v41, v41, v132, vcc
	v_cmp_gt_i32_e32 vcc, 57, v64
	s_or_b64 vcc, s[24:25], vcc
	s_nop 0
	v_cndmask_b32_e32 v61, v62, v132, vcc
	v_cmp_gt_i32_e32 vcc, 26, v64
	s_or_b64 vcc, s[22:23], vcc
	s_nop 0
	v_cndmask_b32_e32 v36, v36, v132, vcc
	v_cmp_gt_i32_e32 vcc, 58, v64
	s_or_b64 vcc, s[24:25], vcc
	s_nop 0
	v_cndmask_b32_e32 v42, v63, v132, vcc
	v_cmp_gt_i32_e32 vcc, 27, v64
	s_or_b64 vcc, s[22:23], vcc
	s_nop 0
	v_cndmask_b32_e32 v37, v37, v132, vcc
	v_cmp_gt_i32_e32 vcc, 59, v64
	s_or_b64 vcc, s[24:25], vcc
	s_nop 0
	v_cndmask_b32_e32 v43, v43, v132, vcc
	s_branch .LBB0_2818

.LBB0_2825:
	s_add_i32 s27, s79, 2
	s_cmp_ge_i32 s27, s47
	s_waitcnt lgkmcnt(0)
	s_barrier
	s_cbranch_scc1 .LBB0_2827
	v_mov_b32_e32 v34, s28
	ds_read_b32 v34, v34
	v_mov_b32_e32 v109, v99
	s_waitcnt lgkmcnt(0)
	v_readfirstlane_b32 s27, v34
	s_lshl_b32 vcc_lo, s27, 6
	s_ashr_i32 vcc_hi, vcc_lo, 31
	s_lshl_b64 vcc, vcc, 9
	s_add_u32 vcc_lo, s31, vcc_lo
	s_addc_u32 vcc_hi, s46, vcc_hi
	v_lshl_add_u64 v[34:35], vcc, 0, v[104:105]
	v_lshl_add_u64 v[36:37], vcc, 0, v[106:107]
	v_lshl_add_u64 v[34:35], s[70:71], 1, v[34:35]
	v_lshl_add_u64 v[36:37], s[72:73], 1, v[36:37]
	v_lshl_add_u64 v[36:37], v[36:37], 0, v[108:109]
	s_waitcnt vmcnt(0)
	global_load_dwordx4 v[82:85], v[34:35], off
	global_load_dwordx4 v[86:89], v[36:37], off offset:256

.LBB0_2829:
	s_and_b64 vcc, exec, s[20:21]
	s_waitcnt lgkmcnt(0)
	s_barrier
	s_cbranch_vccz .LBB0_2831
	s_mul_i32 s6, s5, 0x108
	s_add_i32 s10, s36, s6
	s_add_i32 s6, s10, 0x4c40
	v_mov_b32_e32 v2, s6
	s_add_i32 s6, s10, 0x5060
	v_mov_b32_e32 v4, s6
	s_add_i32 s6, s10, 0x5480
	v_mov_b32_e32 v5, s6
	s_add_i32 s6, s10, 0x58a0
	v_mov_b32_e32 v6, s6
	s_add_i32 s6, s10, 0x5cc0
	ds_read2_b32 v[2:3], v2 offset1:1
	ds_read2_b32 v[8:9], v4 offset1:1
	ds_read2_b32 v[10:11], v5 offset1:1
	ds_read2_b32 v[12:13], v6 offset1:1
	v_mov_b32_e32 v4, s6
	s_add_i32 s6, s10, 0x60e0
	v_mov_b32_e32 v5, s6
	s_add_i32 s6, s10, 0x6500
	v_mov_b32_e32 v6, s6
	s_add_i32 s6, s10, 0x6920
	v_mov_b32_e32 v7, s6
	ds_read2_b32 v[14:15], v4 offset1:1
	ds_read2_b32 v[16:17], v5 offset1:1
	ds_read2_b32 v[18:19], v6 offset1:1
	ds_read2_b32 v[20:21], v7 offset1:1
	s_waitcnt lgkmcnt(6)
	v_max3_f32 v4, v2, s35, v8
	s_waitcnt lgkmcnt(4)
	v_max3_f32 v4, v4, v10, v12
	s_waitcnt lgkmcnt(2)
	v_max3_f32 v4, v4, v14, v16
	v_readlane_b32 s12, v228, 25
	s_waitcnt lgkmcnt(0)
	v_max3_f32 v4, v4, v18, v20
	v_sub_f32_e32 v2, v2, v4
	v_mul_f32_e32 v2, 0x3fb8aa3b, v2
	v_exp_f32_e32 v7, v2
	v_sub_f32_e32 v2, v8, v4
	v_mul_f32_e32 v2, 0x3fb8aa3b, v2
	v_exp_f32_e32 v6, v2
	v_mov_b32_e32 v2, v9
	v_sub_f32_e32 v8, v10, v4
	v_sub_f32_e32 v9, v12, v4
	v_mul_f32_e32 v8, 0x3fb8aa3b, v8
	v_mul_f32_e32 v9, 0x3fb8aa3b, v9
	v_exp_f32_e32 v8, v8
	v_exp_f32_e32 v9, v9
	v_mov_b32_e32 v12, v11
	v_sub_f32_e32 v10, v14, v4
	v_sub_f32_e32 v11, v16, v4
	v_mul_f32_e32 v10, 0x3fb8aa3b, v10
	v_mul_f32_e32 v11, 0x3fb8aa3b, v11
	v_pk_mul_f32 v[2:3], v[2:3], v[6:7]
	v_exp_f32_e32 v10, v10
	v_exp_f32_e32 v11, v11
	v_add_f32_e32 v3, 0, v3
	v_add_f32_e32 v22, v2, v3
	v_pk_mul_f32 v[2:3], v[8:9], v[12:13]
	v_mov_b32_e32 v16, v15
	v_add_f32_e32 v2, v2, v22
	s_add_i32 s6, s10, 0x6d40
	s_lshl_b32 s11, s5, 8
	s_add_i32 s5, s5, s12
	v_add_f32_e32 v14, v2, v3
	v_pk_mul_f32 v[2:3], v[10:11], v[16:17]
	v_mov_b32_e32 v16, s6
	s_add_i32 s6, s10, 0x7160
	s_mul_i32 s12, s5, 3
	v_sub_f32_e32 v12, v18, v4
	v_sub_f32_e32 v4, v20, v4
	v_mov_b32_e32 v20, v19
	v_mov_b32_e32 v19, s6
	s_add_i32 s6, s10, 0x7580
	s_ashr_i32 s13, s12, 31
	v_add_u32_e32 v5, s10, v102
	v_mov_b32_e32 v22, s6
	s_add_i32 s6, s10, 0x79a0
	s_add_i32 s7, s10, 0x7dc0
	s_add_i32 s8, s10, 0x81e0
	s_add_i32 s9, s10, 0x8600
	s_add_i32 s10, s10, 0x8a20
	s_add_i32 s11, s36, s11
	s_lshl_b64 s[12:13], s[12:13], 2
	v_add_f32_e32 v2, v14, v2
	s_add_u32 s12, s18, s12
	v_add_f32_e32 v18, v2, v3
	s_addc_u32 s13, s19, s13
	v_mov_b32_e32 v2, s12
	s_movk_i32 s12, 0x1000
	v_mov_b32_e32 v3, s13
	v_add_co_u32_e32 v2, vcc, s12, v2
	v_mul_f32_e32 v4, 0x3fb8aa3b, v4
	s_nop 0
	v_addc_co_u32_e32 v3, vcc, 0, v3, vcc
	v_exp_f32_e32 v13, v4
	global_load_dwordx3 v[2:4], v[2:3], off offset:1024
	v_mul_f32_e32 v12, 0x3fb8aa3b, v12
	v_exp_f32_e32 v12, v12
	v_mov_b32_e32 v24, s6
	v_mov_b32_e32 v28, s8
	v_mov_b32_e32 v29, s9
	v_pk_mul_f32 v[14:15], v[12:13], v[20:21]
	ds_read2_b32 v[16:17], v16 offset1:1
	ds_read2_b32 v[20:21], v19 offset1:1
	ds_read2_b32 v[22:23], v22 offset1:1
	ds_read2_b32 v[24:25], v24 offset1:1
	v_mov_b32_e32 v19, s7
	v_mov_b32_e32 v30, s10
	ds_read2_b32 v[26:27], v19 offset1:1
	ds_read2_b32 v[38:39], v28 offset1:1
	ds_read2_b32 v[40:41], v29 offset1:1
	ds_read2_b32 v[42:43], v30 offset1:1
	v_add_f32_e32 v14, v18, v14
	s_waitcnt lgkmcnt(0)
	v_max3_f32 v18, v16, s35, v20
	v_max3_f32 v18, v18, v22, v24
	v_max3_f32 v18, v18, v26, v38
	v_max3_f32 v28, v18, v40, v42
	v_sub_f32_e32 v16, v16, v28
	v_mul_f32_e32 v16, 0x3fb8aa3b, v16
	v_exp_f32_e32 v19, v16
	v_sub_f32_e32 v16, v20, v28
	v_mul_f32_e32 v16, 0x3fb8aa3b, v16
	v_exp_f32_e32 v18, v16
	v_add_f32_e32 v14, v14, v15
	v_mov_b32_e32 v16, v21
	v_max_f32_e32 v44, 0xda24260, v14
	v_pk_mul_f32 v[14:15], v[16:17], v[18:19]
	v_sub_f32_e32 v16, v22, v28
	v_sub_f32_e32 v17, v24, v28
	v_mul_f32_e32 v16, 0x3fb8aa3b, v16
	v_mul_f32_e32 v17, 0x3fb8aa3b, v17
	v_exp_f32_e32 v16, v16
	v_exp_f32_e32 v17, v17
	v_add_f32_e32 v15, 0, v15
	v_mov_b32_e32 v24, v23
	v_add_f32_e32 v20, v14, v15
	v_pk_mul_f32 v[14:15], v[16:17], v[24:25]
	v_sub_f32_e32 v21, v40, v28
	v_add_f32_e32 v14, v14, v20
	v_add_f32_e32 v15, v14, v15
	v_sub_f32_e32 v14, v26, v28
	v_mul_f32_e32 v14, 0x3fb8aa3b, v14
	v_exp_f32_e32 v22, v14
	v_sub_f32_e32 v14, v38, v28
	v_mul_f32_e32 v14, 0x3fb8aa3b, v14
	v_exp_f32_e32 v23, v14
	v_mov_b32_e32 v38, v27
	v_mul_f32_e32 v21, 0x3fb8aa3b, v21
	ds_read_b32 v24, v5 offset:24808
	ds_read_b32 v20, v5 offset:25864
	ds_read_b32 v14, v5 offset:26920
	ds_read_b32 v37, v5 offset:27976
	ds_read_b32 v35, v5 offset:29032
	ds_read_b32 v33, v5 offset:30088
	ds_read_b32 v31, v5 offset:31144
	ds_read_b32 v29, v5 offset:32200
	v_pk_mul_f32 v[26:27], v[22:23], v[38:39]
	v_lshlrev_b32_e32 v98, 1, v1
	v_add_f32_e32 v15, v15, v26
	v_exp_f32_e32 v26, v21
	v_sub_f32_e32 v21, v42, v28
	v_mul_f32_e32 v21, 0x3fb8aa3b, v21
	v_add_f32_e32 v15, v15, v27
	v_exp_f32_e32 v27, v21
	v_add_u32_e32 v21, s11, v102
	v_add_u32_e32 v21, 64, v21
	ds_read2st64_b32 v[38:39], v21 offset0:44 offset1:48
	v_mov_b32_e32 v42, v41
	v_pk_mul_f32 v[40:41], v[26:27], v[42:43]
	ds_read2st64_b32 v[42:43], v21 offset0:52 offset1:56
	v_add_f32_e32 v15, v15, v40
	v_add_f32_e32 v45, v15, v41
	ds_read2st64_b32 v[40:41], v21 offset0:60 offset1:64
	s_waitcnt lgkmcnt(0)
	v_add_f32_e32 v15, 0, v38
	v_add_f32_e32 v15, v15, v39
	ds_read2st64_b32 v[38:39], v21 offset0:68 offset1:72
	v_add_f32_e32 v15, v15, v42
	v_add_f32_e32 v15, v15, v43
	v_add_f32_e32 v15, v15, v40
	s_waitcnt lgkmcnt(0)
	v_mov_b32_e32 v42, v39
	s_waitcnt vmcnt(0)
	v_mul_f32_e32 v2, 0xbfb8aa3b, v2
	v_exp_f32_e32 v43, v2
	v_add_f32_e32 v2, v15, v41
	v_add_f32_e32 v100, v2, v38
	ds_read_b32 v36, v5 offset:19528
	ds_read_b32 v34, v5 offset:20584
	ds_read_b32 v32, v5 offset:21640
	ds_read_b32 v30, v5 offset:22696
	ds_read_b32 v28, v5 offset:23752
	ds_read_b32 v25, v5 offset:33256
	ds_read_b32 v21, v5 offset:34312
	ds_read_b32 v15, v5 offset:35368
	v_pk_add_f32 v[38:39], v[100:101], v[42:43]
	v_max_f32_e32 v5, 0xda24260, v45
	v_div_scale_f32 v2, s[6:7], v39, v39, 1.0
	v_rcp_f32_e32 v40, v2
	v_mul_f32_e32 v4, 0xbfb8aa3b, v4
	v_fma_f32 v41, -v2, v40, 1.0
	v_fmac_f32_e32 v40, v41, v40
	v_div_scale_f32 v41, vcc, 1.0, v39, 1.0
	v_mul_f32_e32 v42, v41, v40
	v_fma_f32 v43, -v2, v42, v41
	v_fmac_f32_e32 v42, v43, v40
	v_fma_f32 v2, -v2, v42, v41
	v_div_fmas_f32 v2, v2, v40, v42
	v_div_fixup_f32 v39, v2, v39, 1.0
	v_mul_f32_e32 v40, 0xbfb8aa3b, v3
	v_mov_b32_e32 v2, v7
	v_mov_b32_e32 v3, v19
	s_waitcnt lgkmcnt(7)
	v_pk_fma_f32 v[2:3], v[36:37], v[2:3], 0 op_sel_hi:[1,1,0]
	v_mov_b32_e32 v7, v18
	s_waitcnt lgkmcnt(6)
	v_pk_fma_f32 v[2:3], v[34:35], v[6:7], v[2:3]
	v_mov_b32_e32 v6, v8
	v_mov_b32_e32 v7, v16
	s_waitcnt lgkmcnt(5)
	v_pk_fma_f32 v[2:3], v[6:7], v[32:33], v[2:3]
	v_mov_b32_e32 v16, v9
	s_waitcnt lgkmcnt(4)
	v_pk_fma_f32 v[2:3], v[16:17], v[30:31], v[2:3]
	v_mov_b32_e32 v6, v10
	v_mov_b32_e32 v7, v22
	s_waitcnt lgkmcnt(3)
	v_pk_fma_f32 v[2:3], v[6:7], v[28:29], v[2:3]
	v_mov_b32_e32 v22, v11
	s_waitcnt lgkmcnt(2)
	v_pk_fma_f32 v[2:3], v[22:23], v[24:25], v[2:3]
	v_mov_b32_e32 v6, v12
	v_mov_b32_e32 v7, v26
	s_waitcnt lgkmcnt(1)
	v_pk_fma_f32 v[2:3], v[6:7], v[20:21], v[2:3]
	v_mov_b32_e32 v26, v13
	s_waitcnt lgkmcnt(0)
	v_pk_fma_f32 v[2:3], v[26:27], v[14:15], v[2:3]
	v_exp_f32_e32 v7, v4
	v_div_scale_f32 v8, s[6:7], v5, v5, v3
	v_rcp_f32_e32 v9, v8
	v_exp_f32_e32 v6, v40
	v_fma_f32 v4, -v8, v9, 1.0
	v_fmac_f32_e32 v9, v4, v9
	v_div_scale_f32 v4, vcc, v3, v5, v3
	v_mul_f32_e32 v10, v4, v9
	v_fma_f32 v11, -v8, v10, v4
	v_fmac_f32_e32 v10, v11, v9
	v_fma_f32 v4, -v8, v10, v4
	v_div_scale_f32 v8, s[6:7], v44, v44, v2
	v_rcp_f32_e32 v11, v8
	v_div_fmas_f32 v4, v4, v9, v10
	v_div_fixup_f32 v3, v4, v5, v3
	v_fma_f32 v4, -v8, v11, 1.0
	v_fmac_f32_e32 v11, v4, v11
	v_div_scale_f32 v4, vcc, v2, v44, v2
	v_mul_f32_e32 v9, v4, v11
	v_fma_f32 v5, -v8, v9, v4
	v_fmac_f32_e32 v9, v5, v11
	v_fma_f32 v8, -v8, v9, v4
	v_pk_add_f32 v[4:5], v[6:7], 1.0 op_sel_hi:[1,0]
	v_div_fmas_f32 v8, v8, v11, v9
	v_div_scale_f32 v6, s[6:7], v5, v5, 1.0
	v_rcp_f32_e32 v7, v6
	v_div_fixup_f32 v2, v8, v44, v2
	v_fma_f32 v8, -v6, v7, 1.0
	v_fmac_f32_e32 v7, v8, v7
	v_div_scale_f32 v8, vcc, 1.0, v5, 1.0
	v_mul_f32_e32 v9, v8, v7
	v_fma_f32 v10, -v6, v9, v8
	v_fmac_f32_e32 v9, v10, v7
	v_fma_f32 v6, -v6, v9, v8
	v_div_scale_f32 v8, s[6:7], v4, v4, 1.0
	v_rcp_f32_e32 v10, v8
	v_div_fmas_f32 v6, v6, v7, v9
	v_div_fixup_f32 v5, v6, v5, 1.0
	s_lshl_b32 s6, s5, 6
	v_fma_f32 v6, -v8, v10, 1.0
	v_fmac_f32_e32 v10, v6, v10
	v_div_scale_f32 v6, vcc, 1.0, v4, 1.0
	v_mul_f32_e32 v7, v6, v10
	v_fma_f32 v9, -v8, v7, v6
	v_fmac_f32_e32 v7, v9, v10
	v_fma_f32 v6, -v8, v7, v6
	v_div_fmas_f32 v6, v6, v10, v7
	v_div_fixup_f32 v4, v6, v4, 1.0
	s_ashr_i32 s7, s6, 31
	v_pk_mul_f32 v[2:3], v[2:3], v[4:5]
	s_add_u32 s5, s66, s60
	v_fma_f32 v2, v38, v39, v2
	s_addc_u32 s8, s67, s61
	s_lshl_b64 s[6:7], s[6:7], 1
	v_add_f32_e32 v2, v2, v3
	s_add_u32 s6, s5, s6
	v_bfe_u32 v3, v2, 16, 1
	s_addc_u32 s7, s8, s7
	v_add3_u32 v4, v2, v3, s2
	v_lshl_add_u64 v[2:3], s[6:7], 0, v[98:99]
	v_add_co_u32_e32 v2, vcc, 0xdc00000, v2
	s_nop 1
	v_addc_co_u32_e32 v3, vcc, 0, v3, vcc
	global_store_short_d16_hi v[2:3], v4, off

.LBB0_2873:
	s_or_b64 exec, exec, s[10:11]
	s_and_saveexec_b64 s[8:9], s[6:7]
	ds_write_b32 v141, v35 offset:33024
	s_or_b64 exec, exec, s[8:9]
	s_waitcnt lgkmcnt(0)
	ds_read_b32 v36, v1 offset:33024
	ds_read2_b32 v[34:35], v142 offset1:32
	v_add_u32_e32 v106, 0x9000, v159
	v_add_u32_e32 v107, 0x9000, v158
	v_add_u32_e32 v108, 0x9000, v157
	v_add_u32_e32 v109, 0x9000, v156
	s_waitcnt lgkmcnt(0)
	v_fma_f32 v18, v18, v36, v34
	v_fmac_f32_e32 v35, v2, v36
	ds_write2_b32 v142, v18, v35 offset1:32
	ds_read_b32 v2, v1 offset:33028
	ds_read2_b32 v[34:35], v106 offset1:32
	v_add_u32_e32 v110, 0x9000, v155
	v_add_u32_e32 v112, 0x9000, v154
	v_add_u32_e32 v113, 0x9000, v153
	v_add_u32_e32 v114, 0x9000, v152
	s_waitcnt lgkmcnt(0)
	v_fma_f32 v18, v19, v2, v34
	v_fmac_f32_e32 v35, v3, v2
	ds_write2_b32 v106, v18, v35 offset1:32
	ds_read_b32 v18, v1 offset:33032
	ds_read2_b32 v[2:3], v107 offset1:32
	v_add_u32_e32 v115, 0x9000, v151
	v_add_u32_e32 v117, 0x9000, v150
	v_add_u32_e32 v118, 0x9000, v149
	v_add_u32_e32 v91, 0x9000, v148
	s_waitcnt lgkmcnt(0)
	v_fma_f32 v2, v20, v18, v2
	v_fmac_f32_e32 v3, v4, v18
	ds_write2_b32 v107, v2, v3 offset1:32
	ds_read_b32 v4, v1 offset:33036
	ds_read2_b32 v[2:3], v108 offset1:32
	v_add_u32_e32 v102, 0x9000, v147
	v_add_u32_e32 v111, 0x9000, v146
	v_add_u32_e32 v116, 0x9000, v145
	s_add_u32 s8, s68, s30
	s_waitcnt lgkmcnt(0)
	v_fma_f32 v2, v21, v4, v2
	v_fmac_f32_e32 v3, v5, v4
	ds_write2_b32 v108, v2, v3 offset1:32
	ds_read_b32 v4, v1 offset:33056
	ds_read2_b32 v[2:3], v109 offset1:32
	s_addc_u32 s9, s69, 0
	s_add_u32 s8, s8, s49
	s_addc_u32 s9, s9, 0
	s_add_u32 s12, s8, 0x28000000
	s_waitcnt lgkmcnt(0)
	v_fma_f32 v2, v22, v4, v2
	v_fmac_f32_e32 v3, v6, v4
	ds_write2_b32 v109, v2, v3 offset1:32
	ds_read_b32 v4, v1 offset:33060
	ds_read2_b32 v[2:3], v110 offset1:32
	s_addc_u32 s13, s9, 0
	s_lshl_b32 s10, s65, 15
	s_add_u32 s8, s12, s10
	s_addc_u32 s9, s13, 0
	s_waitcnt lgkmcnt(0)
	v_fma_f32 v2, v23, v4, v2
	v_fmac_f32_e32 v3, v7, v4
	ds_write2_b32 v110, v2, v3 offset1:32
	ds_read_b32 v4, v1 offset:33064
	ds_read2_b32 v[2:3], v112 offset1:32
	s_cmp_eq_u32 s65, 0
	s_waitcnt lgkmcnt(0)
	v_fma_f32 v2, v24, v4, v2
	v_fmac_f32_e32 v3, v8, v4
	ds_write2_b32 v112, v2, v3 offset1:32
	ds_read_b32 v4, v1 offset:33068
	ds_read2_b32 v[2:3], v113 offset1:32
	s_waitcnt lgkmcnt(0)
	v_fma_f32 v2, v25, v4, v2
	v_fmac_f32_e32 v3, v9, v4
	ds_write2_b32 v113, v2, v3 offset1:32
	ds_read_b32 v4, v1 offset:33088
	ds_read2_b32 v[2:3], v114 offset1:32
	s_waitcnt lgkmcnt(0)
	v_fma_f32 v2, v26, v4, v2
	v_fmac_f32_e32 v3, v10, v4
	ds_write2_b32 v114, v2, v3 offset1:32
	ds_read_b32 v4, v1 offset:33092
	ds_read2_b32 v[2:3], v115 offset1:32
	s_waitcnt lgkmcnt(0)
	v_fma_f32 v2, v27, v4, v2
	v_fmac_f32_e32 v3, v11, v4
	ds_write2_b32 v115, v2, v3 offset1:32
	ds_read_b32 v4, v1 offset:33096
	ds_read2_b32 v[2:3], v117 offset1:32
	s_waitcnt lgkmcnt(0)
	v_fma_f32 v2, v28, v4, v2
	v_fmac_f32_e32 v3, v12, v4
	ds_write2_b32 v117, v2, v3 offset1:32
	ds_read_b32 v4, v1 offset:33100
	ds_read2_b32 v[2:3], v118 offset1:32
	s_waitcnt lgkmcnt(0)
	v_fma_f32 v2, v29, v4, v2
	v_fmac_f32_e32 v3, v13, v4
	ds_write2_b32 v118, v2, v3 offset1:32
	ds_read_b32 v4, v1 offset:33120
	ds_read2_b32 v[2:3], v91 offset1:32
	s_waitcnt lgkmcnt(0)
	v_fma_f32 v2, v30, v4, v2
	v_fmac_f32_e32 v3, v14, v4
	ds_write2_b32 v91, v2, v3 offset1:32
	ds_read_b32 v4, v1 offset:33124
	ds_read2_b32 v[2:3], v102 offset1:32
	s_waitcnt lgkmcnt(0)
	v_fma_f32 v2, v31, v4, v2
	v_fmac_f32_e32 v3, v15, v4
	ds_write2_b32 v102, v2, v3 offset1:32
	ds_read_b32 v4, v1 offset:33128
	ds_read2_b32 v[2:3], v111 offset1:32
	s_waitcnt lgkmcnt(0)
	v_fma_f32 v2, v32, v4, v2
	v_fmac_f32_e32 v3, v16, v4
	ds_write2_b32 v111, v2, v3 offset1:32
	ds_read_b32 v4, v1 offset:33132
	ds_read2_b32 v[2:3], v116 offset1:32
	s_waitcnt lgkmcnt(0)
	v_fma_f32 v2, v33, v4, v2
	v_fmac_f32_e32 v3, v17, v4
	ds_write2_b32 v116, v2, v3 offset1:32
	v_mov_b32_e32 v2, v139
	s_waitcnt lgkmcnt(0)
	s_nop 0
	v_ashrrev_i32_e32 v4, 5, v2
	v_lshlrev_b32_e32 v3, 3, v2
	v_lshlrev_b32_e32 v6, 3, v4
	v_and_b32_e32 v5, 24, v3
	v_ashrrev_i32_e32 v7, 31, v6
	v_ashrrev_i32_e32 v3, 31, v2
	v_lshl_add_u64 v[6:7], v[6:7], 1, v[94:95]
	v_lshlrev_b64 v[94:95], 9, v[2:3]
	global_load_dwordx4 v[66:69], v[6:7], off
	global_load_dwordx4 v[70:73], v[6:7], off offset:32
	global_load_dwordx4 v[74:77], v[6:7], off offset:64
	global_load_dwordx4 v[78:81], v[6:7], off offset:96
	v_lshl_add_u64 v[6:7], s[8:9], 0, v[94:95]
	v_lshl_add_u64 v[6:7], s[70:71], 1, v[6:7]
	v_ashrrev_i32_e32 v3, 2, v2
	s_waitcnt lgkmcnt(0)
	s_barrier
	s_waitcnt vmcnt(0)
	global_load_dwordx4 v[82:85], v[6:7], off
	v_add_u32_e32 v6, s48, v3
	v_ashrrev_i32_e32 v7, 31, v6
	v_lshlrev_b64 v[96:97], 9, v[6:7]
	v_lshl_add_u64 v[6:7], s[8:9], 0, v[96:97]
	v_lshl_add_u64 v[6:7], s[72:73], 1, v[6:7]
	v_lshlrev_b32_e32 v98, 1, v5
	v_lshl_add_u64 v[6:7], v[6:7], 0, v[98:99]
	global_load_dwordx4 v[86:89], v[6:7], off offset:256
	v_lshl_add_u32 v119, v2, 4, s83
	s_waitcnt vmcnt(0) lgkmcnt(0)
	ds_write_b128 v119, v[82:85]
	ds_write_b128 v119, v[86:89] offset:16384
	s_waitcnt lgkmcnt(0)
	s_barrier
	s_cbranch_scc1 .LBB0_2877
	s_lshl_b32 s8, s52, 9
	s_add_u32 s8, s12, s8
	s_addc_u32 s9, s13, 0
	s_add_u32 s8, s8, 0xffff8000
	s_addc_u32 s9, s9, -1
	v_lshl_add_u64 v[6:7], s[8:9], 0, v[94:95]
	v_lshl_add_u64 v[8:9], s[8:9], 0, v[96:97]
	v_lshl_add_u64 v[6:7], s[70:71], 1, v[6:7]
	v_lshl_add_u64 v[8:9], s[72:73], 1, v[8:9]
	v_lshl_add_u64 v[8:9], v[8:9], 0, v[98:99]
	global_load_dwordx4 v[82:85], v[6:7], off
	global_load_dwordx4 v[86:89], v[8:9], off offset:256

.LBB0_2878:
	s_and_b32 s18, s15, 0x2000
	v_add_u32_e32 v100, s18, v122
	ds_read_b128 v[34:37], v100
	ds_read_b128 v[150:153], v100 offset:2048
	ds_read_b128 v[230:233], v100 offset:512
	ds_read_b128 v[234:237], v100 offset:2560
	ds_read_b128 v[238:241], v100 offset:4096
	ds_read_b128 v[242:245], v100 offset:4608
	ds_read_b128 v[246:249], v100 offset:6144
	ds_read_b128 v[250:253], v100 offset:6656
	s_waitcnt lgkmcnt(6)
	v_mfma_f32_32x32x16_bf16 v[50:65], v[34:37], v[66:69], 0
	v_mfma_f32_32x32x16_bf16 v[50:65], v[150:153], v[70:73], v[50:65]
	s_waitcnt lgkmcnt(4)
	v_mfma_f32_32x32x16_bf16 v[34:49], v[230:233], v[66:69], 0
	v_mfma_f32_32x32x16_bf16 v[34:49], v[234:237], v[70:73], v[34:49]
	s_waitcnt lgkmcnt(3)
	v_mfma_f32_32x32x16_bf16 v[50:65], v[238:241], v[74:77], v[50:65]
	s_waitcnt lgkmcnt(2)
	v_mfma_f32_32x32x16_bf16 v[34:49], v[242:245], v[74:77], v[34:49]
	s_waitcnt lgkmcnt(1)
	v_mfma_f32_32x32x16_bf16 v[50:65], v[246:249], v[78:81], v[50:65]
	s_waitcnt lgkmcnt(0)
	v_mfma_f32_32x32x16_bf16 v[34:49], v[250:253], v[78:81], v[34:49]
	v_cvt_f32_i32_e32 v100, v148
	v_subrev_u32_e32 v152, 63, v147
	s_movk_i32 s10, 0x1c1
	v_cmp_gt_u32_e32 vcc, s10, v152
	v_fma_f32 v100, v90, v100, v121
	v_sub_f32_e32 v100, v100, v149
	v_add_f32_e32 v150, v144, v100
	v_add_f32_e32 v151, v90, v150
	v_add_f32_e32 v153, v143, v100
	v_pk_add_f32 v[50:51], v[150:151], v[50:51]
	v_pk_add_f32 v[150:151], v[104:105], v[150:151] op_sel_hi:[1,0]
	s_cmp_eq_u64 vcc, exec
	v_pk_add_f32 v[52:53], v[150:151], v[52:53]
	v_add_f32_e32 v150, v144, v153
	v_add_f32_e32 v151, v90, v150
	v_pk_add_f32 v[34:35], v[150:151], v[34:35]
	v_pk_add_f32 v[150:151], v[104:105], v[150:151] op_sel_hi:[1,0]
	s_nop 0
	v_pk_add_f32 v[36:37], v[150:151], v[36:37]
	v_add_f32_e32 v150, v125, v100
	v_add_f32_e32 v151, v90, v150
	v_pk_add_f32 v[54:55], v[150:151], v[54:55]
	v_pk_add_f32 v[150:151], v[104:105], v[150:151] op_sel_hi:[1,0]
	s_nop 0
	v_pk_add_f32 v[56:57], v[150:151], v[56:57]
	v_add_f32_e32 v150, v125, v153
	v_add_f32_e32 v151, v90, v150
	v_pk_add_f32 v[38:39], v[150:151], v[38:39]
	v_pk_add_f32 v[150:151], v[104:105], v[150:151] op_sel_hi:[1,0]
	s_nop 0
	v_pk_add_f32 v[40:41], v[150:151], v[40:41]
	v_add_f32_e32 v150, v92, v100
	v_add_f32_e32 v151, v90, v150
	v_pk_add_f32 v[58:59], v[150:151], v[58:59]
	v_pk_add_f32 v[150:151], v[104:105], v[150:151] op_sel_hi:[1,0]
	s_nop 0
	v_pk_add_f32 v[60:61], v[150:151], v[60:61]
	v_add_f32_e32 v150, v92, v153
	v_add_f32_e32 v151, v90, v150
	v_pk_add_f32 v[42:43], v[150:151], v[42:43]
	v_pk_add_f32 v[150:151], v[104:105], v[150:151] op_sel_hi:[1,0]
	s_nop 0
	v_pk_add_f32 v[44:45], v[150:151], v[44:45]
	v_add_f32_e32 v150, v103, v100
	v_add_f32_e32 v151, v90, v150
	v_pk_add_f32 v[62:63], v[150:151], v[62:63]
	v_pk_add_f32 v[150:151], v[104:105], v[150:151] op_sel_hi:[1,0]
	s_nop 0
	v_pk_add_f32 v[64:65], v[150:151], v[64:65]
	v_add_f32_e32 v150, v103, v153
	v_add_f32_e32 v151, v90, v150
	v_pk_add_f32 v[46:47], v[150:151], v[46:47]
	v_pk_add_f32 v[150:151], v[104:105], v[150:151] op_sel_hi:[1,0]
	s_nop 0
	v_pk_add_f32 v[48:49], v[150:151], v[48:49]
	s_cbranch_scc1 .LBB0_2880
	v_add_u32_e32 v100, v146, v147
	s_movk_i32 s10, 0x200
	v_add_u32_e32 v150, 0xfffffdff, v100
	v_cmp_gt_u32_e32 vcc, s10, v100
	v_add_u32_e32 v151, 0xfffffdfe, v100
	v_add_u32_e32 v152, 0xfffffdc7, v100
	v_cndmask_b32_e32 v50, v132, v50, vcc
	v_cmp_lt_u32_e32 vcc, s34, v150
	v_add_u32_e32 v150, 0xfffffdfd, v100
	v_add_u32_e32 v153, 0xfffffdc8, v100
	v_cndmask_b32_e32 v51, v132, v51, vcc
	v_cmp_lt_u32_e32 vcc, s34, v151
	v_add_u32_e32 v151, 0xfffffdf8, v100
	v_add_u32_e32 v154, 0xfffffdcd, v100
	v_cndmask_b32_e32 v52, v132, v52, vcc
	v_cmp_lt_u32_e32 vcc, s34, v150
	v_add_u32_e32 v150, 0xfffffdf7, v100
	v_add_u32_e32 v155, 0xfffffdce, v100
	v_cndmask_b32_e32 v53, v132, v53, vcc
	v_cmp_lt_u32_e32 vcc, s34, v151
	v_add_u32_e32 v151, 0xfffffdf6, v100
	v_add_u32_e32 v156, 0xfffffdcf, v100
	v_cndmask_b32_e32 v54, v132, v54, vcc
	v_cmp_lt_u32_e32 vcc, s34, v150
	v_add_u32_e32 v150, 0xfffffdf5, v100
	v_add_u32_e32 v157, 0xfffffdd0, v100
	v_cndmask_b32_e32 v55, v132, v55, vcc
	v_cmp_lt_u32_e32 vcc, s34, v151
	v_add_u32_e32 v151, 0xfffffdf0, v100
	v_add_u32_e32 v158, 0xfffffdd5, v100
	v_cndmask_b32_e32 v56, v132, v56, vcc
	v_cmp_lt_u32_e32 vcc, s34, v150
	v_add_u32_e32 v150, 0xfffffdef, v100
	v_add_u32_e32 v159, 0xfffffdd6, v100
	v_cndmask_b32_e32 v57, v132, v57, vcc
	v_cmp_lt_u32_e32 vcc, s34, v151
	v_add_u32_e32 v151, 0xfffffdee, v100
	v_add_u32_e32 v160, 0xfffffdd7, v100
	v_cndmask_b32_e32 v58, v132, v58, vcc
	v_cmp_lt_u32_e32 vcc, s34, v150
	v_add_u32_e32 v150, 0xfffffded, v100
	v_add_u32_e32 v161, 0xfffffdd8, v100
	v_cndmask_b32_e32 v59, v132, v59, vcc
	v_cmp_lt_u32_e32 vcc, s34, v151
	v_add_u32_e32 v151, 0xfffffde8, v100
	v_add_u32_e32 v162, 0xfffffddd, v100
	v_cndmask_b32_e32 v60, v132, v60, vcc
	v_cmp_lt_u32_e32 vcc, s34, v150
	v_add_u32_e32 v150, 0xfffffde7, v100
	v_add_u32_e32 v163, 0xfffffdde, v100
	v_cndmask_b32_e32 v61, v132, v61, vcc
	v_cmp_lt_u32_e32 vcc, s34, v151
	v_add_u32_e32 v151, 0xfffffde5, v100
	v_add_u32_e32 v164, 0xfffffddf, v100
	v_cndmask_b32_e32 v62, v132, v62, vcc
	v_cmp_lt_u32_e32 vcc, s34, v150
	v_add_u32_e32 v150, 0xfffffde6, v100
	s_nop 0
	v_cndmask_b32_e32 v63, v132, v63, vcc
	v_cmp_lt_u32_e32 vcc, s34, v151
	v_add_u32_e32 v151, 0xfffffdc6, v100
	s_nop 0
	v_cndmask_b32_e32 v65, v132, v65, vcc
	v_cmp_lt_u32_e32 vcc, s34, v150
	v_add_u32_e32 v150, 0xfffffdc5, v100
	v_add_u32_e32 v100, 0xfffffde0, v100
	v_cndmask_b32_e32 v64, v132, v64, vcc
	v_cmp_lt_u32_e32 vcc, s34, v100
	s_nop 1
	v_cndmask_b32_e32 v34, v132, v34, vcc
	v_cmp_lt_u32_e32 vcc, s34, v164
	s_nop 1
	v_cndmask_b32_e32 v35, v132, v35, vcc
	v_cmp_lt_u32_e32 vcc, s34, v163
	s_nop 1
	v_cndmask_b32_e32 v36, v132, v36, vcc
	v_cmp_lt_u32_e32 vcc, s34, v162
	s_nop 1
	v_cndmask_b32_e32 v37, v132, v37, vcc
	v_cmp_lt_u32_e32 vcc, s34, v161
	s_nop 1
	v_cndmask_b32_e32 v38, v132, v38, vcc
	v_cmp_lt_u32_e32 vcc, s34, v160
	s_nop 1
	v_cndmask_b32_e32 v39, v132, v39, vcc
	v_cmp_lt_u32_e32 vcc, s34, v159
	s_nop 1
	v_cndmask_b32_e32 v40, v132, v40, vcc
	v_cmp_lt_u32_e32 vcc, s34, v158
	s_nop 1
	v_cndmask_b32_e32 v41, v132, v41, vcc
	v_cmp_lt_u32_e32 vcc, s34, v157
	s_nop 1
	v_cndmask_b32_e32 v42, v132, v42, vcc
	v_cmp_lt_u32_e32 vcc, s34, v156
	s_nop 1
	v_cndmask_b32_e32 v43, v132, v43, vcc
	v_cmp_lt_u32_e32 vcc, s34, v155
	s_nop 1
	v_cndmask_b32_e32 v44, v132, v44, vcc
	v_cmp_lt_u32_e32 vcc, s34, v154
	s_nop 1
	v_cndmask_b32_e32 v45, v132, v45, vcc
	v_cmp_lt_u32_e32 vcc, s34, v153
	s_nop 1
	v_cndmask_b32_e32 v46, v132, v46, vcc
	v_cmp_lt_u32_e32 vcc, s34, v152
	s_nop 1
	v_cndmask_b32_e32 v47, v132, v47, vcc
	v_cmp_lt_u32_e32 vcc, s34, v151
	s_nop 1
	v_cndmask_b32_e32 v48, v132, v48, vcc
	v_cmp_lt_u32_e32 vcc, s34, v150
	s_nop 1
	v_cndmask_b32_e32 v49, v132, v49, vcc

.LBB0_2886:
	s_add_i32 s10, s17, 2
	s_cmp_gt_u32 s10, s14
	s_waitcnt lgkmcnt(0)
	s_barrier
	s_cbranch_scc1 .LBB0_2888
	s_add_u32 s10, s12, s16
	s_addc_u32 s11, s13, 0
	s_waitcnt vmcnt(0)
	v_lshl_add_u64 v[84:85], s[10:11], 0, v[96:97]
	v_lshl_add_u64 v[82:83], s[10:11], 0, v[94:95]
	v_lshl_add_u64 v[84:85], s[72:73], 1, v[84:85]
	v_lshl_add_u64 v[82:83], s[70:71], 1, v[82:83]
	v_lshl_add_u64 v[86:87], v[84:85], 0, v[98:99]
	global_load_dwordx4 v[82:85], v[82:83], off
	s_nop 0
	global_load_dwordx4 v[86:89], v[86:87], off offset:256

.LBB0_2892:
	s_or_b64 exec, exec, s[8:9]
	s_and_saveexec_b64 s[8:9], s[6:7]
	ds_write_b32 v141, v35 offset:33024
	s_or_b64 exec, exec, s[8:9]
	s_waitcnt lgkmcnt(0)
	ds_read_b32 v38, v1 offset:33024
	ds_read2_b32 v[34:35], v142 offset1:32
	ds_read2_b32 v[36:37], v106 offset1:32
	s_or_b32 s6, s50, s52
	s_add_u32 s6, s6, s70
	s_addc_u32 s7, 0, s71
	s_waitcnt lgkmcnt(0)
	v_fma_f32 v18, v18, v38, v34
	v_fmac_f32_e32 v35, v2, v38
	ds_write2_b32 v142, v18, v35 offset1:32
	ds_read_b32 v2, v1 offset:33028
	ds_read2_b32 v[34:35], v107 offset1:32
	s_mov_b64 s[8:9], 0xdc00000
	s_waitcnt lgkmcnt(0)
	v_fma_f32 v18, v19, v2, v36
	v_fmac_f32_e32 v37, v3, v2
	ds_write2_b32 v106, v18, v37 offset1:32
	ds_read_b32 v18, v1 offset:33032
	ds_read2_b32 v[2:3], v108 offset1:32
	s_waitcnt lgkmcnt(0)
	v_fma_f32 v19, v20, v18, v34
	v_fmac_f32_e32 v35, v4, v18
	ds_write2_b32 v107, v19, v35 offset1:32
	ds_read_b32 v4, v1 offset:33036
	ds_read2_b32 v[18:19], v109 offset1:32
	s_waitcnt lgkmcnt(0)
	v_fma_f32 v2, v21, v4, v2
	v_fmac_f32_e32 v3, v5, v4
	ds_write2_b32 v108, v2, v3 offset1:32
	ds_read_b32 v4, v1 offset:33056
	ds_read2_b32 v[2:3], v110 offset1:32
	s_waitcnt lgkmcnt(0)
	v_fma_f32 v5, v22, v4, v18
	v_fmac_f32_e32 v19, v6, v4
	ds_write2_b32 v109, v5, v19 offset1:32
	ds_read_b32 v6, v1 offset:33060
	ds_read2_b32 v[4:5], v112 offset1:32
	s_waitcnt lgkmcnt(0)
	v_fma_f32 v2, v23, v6, v2
	v_fmac_f32_e32 v3, v7, v6
	ds_write2_b32 v110, v2, v3 offset1:32
	ds_read_b32 v6, v1 offset:33064
	ds_read2_b32 v[2:3], v113 offset1:32
	v_lshlrev_b32_e32 v7, 3, v139
	s_waitcnt lgkmcnt(0)
	v_fma_f32 v4, v24, v6, v4
	v_fmac_f32_e32 v5, v8, v6
	ds_write2_b32 v112, v4, v5 offset1:32
	ds_read_b32 v6, v1 offset:33068
	ds_read2_b32 v[4:5], v114 offset1:32
	v_and_or_b32 v8, v93, 3, s75
	v_lshlrev_b32_e32 v98, 7, v8
	s_waitcnt lgkmcnt(0)
	v_fma_f32 v2, v25, v6, v2
	v_fmac_f32_e32 v3, v9, v6
	ds_write2_b32 v113, v2, v3 offset1:32
	ds_read_b32 v6, v1 offset:33088
	ds_read2_b32 v[2:3], v115 offset1:32
	v_and_b32_e32 v9, 56, v7
	s_waitcnt lgkmcnt(0)
	v_fma_f32 v4, v26, v6, v4
	v_fmac_f32_e32 v5, v10, v6
	ds_write2_b32 v114, v4, v5 offset1:32
	ds_read_b32 v6, v1 offset:33092
	ds_read2_b32 v[4:5], v117 offset1:32
	s_waitcnt lgkmcnt(0)
	v_fma_f32 v2, v27, v6, v2
	v_fmac_f32_e32 v3, v11, v6
	ds_write2_b32 v115, v2, v3 offset1:32
	ds_read_b32 v6, v1 offset:33096
	ds_read2_b32 v[2:3], v118 offset1:32
	s_waitcnt lgkmcnt(0)
	v_fma_f32 v4, v28, v6, v4
	v_fmac_f32_e32 v5, v12, v6
	ds_write2_b32 v117, v4, v5 offset1:32
	ds_read_b32 v6, v1 offset:33100
	ds_read2_b32 v[4:5], v91 offset1:32
	s_waitcnt lgkmcnt(0)
	v_fma_f32 v2, v29, v6, v2
	v_fmac_f32_e32 v3, v13, v6
	ds_write2_b32 v118, v2, v3 offset1:32
	ds_read_b32 v6, v1 offset:33120
	ds_read2_b32 v[2:3], v102 offset1:32
	s_waitcnt lgkmcnt(0)
	v_fma_f32 v4, v30, v6, v4
	v_fmac_f32_e32 v5, v14, v6
	ds_write2_b32 v91, v4, v5 offset1:32
	ds_read_b32 v6, v1 offset:33124
	ds_read2_b32 v[4:5], v111 offset1:32
	v_lshl_add_u32 v14, v9, 2, s54
	v_lshl_add_u32 v8, v93, 8, v14
	s_waitcnt lgkmcnt(0)
	v_fma_f32 v2, v31, v6, v2
	v_fmac_f32_e32 v3, v15, v6
	ds_write2_b32 v102, v2, v3 offset1:32
	ds_read_b32 v6, v1 offset:33128
	ds_read2_b32 v[2:3], v116 offset1:32
	s_waitcnt lgkmcnt(0)
	v_fma_f32 v4, v32, v6, v4
	v_fmac_f32_e32 v5, v16, v6
	ds_write2_b32 v111, v4, v5 offset1:32
	ds_read_b32 v1, v1 offset:33132
	v_lshl_add_u64 v[6:7], s[68:69], 0, v[98:99]
	v_lshlrev_b32_e32 v98, 1, v9
	v_lshl_add_u64 v[6:7], v[6:7], 0, v[98:99]
	v_lshl_add_u64 v[6:7], v[6:7], 0, s[8:9]
	s_waitcnt lgkmcnt(0)
	v_fma_f32 v2, v33, v1, v2
	v_fmac_f32_e32 v3, v17, v1
	ds_write2_b32 v116, v2, v3 offset1:32
	s_waitcnt lgkmcnt(0)
	ds_read_b128 v[2:5], v8 offset:36864
	ds_read_b128 v[8:11], v8 offset:36880
	s_waitcnt lgkmcnt(0)
	v_bfe_u32 v1, v2, 16, 1
	v_bfe_u32 v12, v3, 16, 1
	v_add3_u32 v1, v2, v1, s2
	v_bfe_u32 v13, v4, 16, 1
	v_bfe_u32 v15, v5, 16, 1
	v_bfe_u32 v16, v8, 16, 1
	v_bfe_u32 v17, v9, 16, 1
	v_bfe_u32 v18, v10, 16, 1
	v_add3_u32 v2, v3, v12, s2
	v_lshrrev_b32_e32 v1, 16, v1
	v_bfe_u32 v19, v11, 16, 1
	v_add3_u32 v3, v4, v13, s2
	v_add3_u32 v4, v5, v15, s2
	v_add3_u32 v5, v8, v16, s2
	v_add3_u32 v8, v9, v17, s2
	v_add3_u32 v9, v10, v18, s2
	v_and_or_b32 v2, v2, s33, v1
	v_lshrrev_b32_e32 v1, 5, v139
	v_add3_u32 v10, v11, v19, s2
	v_lshrrev_b32_e32 v3, 16, v3
	v_lshrrev_b32_e32 v5, 16, v5
	v_lshrrev_b32_e32 v9, 16, v9
	v_or_b32_e32 v12, s6, v1
	v_mov_b32_e32 v13, s7
	v_and_or_b32 v3, v4, s33, v3
	v_and_or_b32 v4, v8, s33, v5
	v_and_or_b32 v5, v10, s33, v9
	v_lshlrev_b64 v[8:9], 11, v[12:13]
	v_lshl_add_u64 v[8:9], v[6:7], 0, v[8:9]
	v_or_b32_e32 v1, 8, v93
	global_store_dwordx4 v[8:9], v[2:5], off
	v_lshl_add_u32 v8, v1, 8, v14
	ds_read_b128 v[2:5], v8 offset:36864
	ds_read_b128 v[8:11], v8 offset:36880
	v_lshrrev_b32_e32 v1, 2, v1
	s_waitcnt lgkmcnt(0)
	v_bfe_u32 v12, v2, 16, 1
	v_add3_u32 v2, v2, v12, s2
	v_bfe_u32 v12, v3, 16, 1
	v_lshrrev_b32_e32 v2, 16, v2
	v_add3_u32 v3, v3, v12, s2
	v_and_or_b32 v2, v3, s33, v2
	v_bfe_u32 v3, v4, 16, 1
	v_add3_u32 v3, v4, v3, s2
	v_bfe_u32 v4, v5, 16, 1
	v_lshrrev_b32_e32 v3, 16, v3
	v_add3_u32 v4, v5, v4, s2
	v_and_or_b32 v3, v4, s33, v3
	v_bfe_u32 v4, v8, 16, 1
	v_add3_u32 v4, v8, v4, s2
	v_bfe_u32 v5, v9, 16, 1
	v_lshrrev_b32_e32 v4, 16, v4
	v_add3_u32 v5, v9, v5, s2
	v_and_or_b32 v4, v5, s33, v4
	v_bfe_u32 v5, v10, 16, 1
	v_add3_u32 v5, v10, v5, s2
	v_bfe_u32 v8, v11, 16, 1
	v_lshrrev_b32_e32 v5, 16, v5
	v_add3_u32 v8, v11, v8, s2
	v_or_b32_e32 v12, s6, v1
	v_and_or_b32 v5, v8, s33, v5
	v_lshlrev_b64 v[8:9], 11, v[12:13]
	v_lshl_add_u64 v[8:9], v[6:7], 0, v[8:9]
	v_or_b32_e32 v1, 16, v93
	global_store_dwordx4 v[8:9], v[2:5], off
	v_lshl_add_u32 v8, v1, 8, v14
	ds_read_b128 v[2:5], v8 offset:36864
	ds_read_b128 v[8:11], v8 offset:36880
	v_lshrrev_b32_e32 v1, 2, v1
	s_waitcnt lgkmcnt(0)
	v_bfe_u32 v12, v2, 16, 1
	v_add3_u32 v2, v2, v12, s2
	v_bfe_u32 v12, v3, 16, 1
	v_lshrrev_b32_e32 v2, 16, v2
	v_add3_u32 v3, v3, v12, s2
	v_and_or_b32 v2, v3, s33, v2
	v_bfe_u32 v3, v4, 16, 1
	v_add3_u32 v3, v4, v3, s2
	v_bfe_u32 v4, v5, 16, 1
	v_lshrrev_b32_e32 v3, 16, v3
	v_add3_u32 v4, v5, v4, s2
	v_and_or_b32 v3, v4, s33, v3
	v_bfe_u32 v4, v8, 16, 1
	v_add3_u32 v4, v8, v4, s2
	v_bfe_u32 v5, v9, 16, 1
	v_lshrrev_b32_e32 v4, 16, v4
	v_add3_u32 v5, v9, v5, s2
	v_and_or_b32 v4, v5, s33, v4
	v_bfe_u32 v5, v10, 16, 1
	v_add3_u32 v5, v10, v5, s2
	v_bfe_u32 v8, v11, 16, 1
	v_lshrrev_b32_e32 v5, 16, v5
	v_add3_u32 v8, v11, v8, s2
	v_or_b32_e32 v12, s6, v1
	v_and_or_b32 v5, v8, s33, v5
	v_lshlrev_b64 v[8:9], 11, v[12:13]
	v_lshl_add_u64 v[8:9], v[6:7], 0, v[8:9]
	v_or_b32_e32 v1, 24, v93
	global_store_dwordx4 v[8:9], v[2:5], off
	v_lshl_add_u32 v8, v1, 8, v14
	ds_read_b128 v[2:5], v8 offset:36864
	ds_read_b128 v[8:11], v8 offset:36880
	v_lshrrev_b32_e32 v1, 2, v1
	s_waitcnt lgkmcnt(0)
	v_bfe_u32 v12, v2, 16, 1
	v_add3_u32 v2, v2, v12, s2
	v_bfe_u32 v12, v3, 16, 1
	v_lshrrev_b32_e32 v2, 16, v2
	v_add3_u32 v3, v3, v12, s2
	v_and_or_b32 v2, v3, s33, v2
	v_bfe_u32 v3, v4, 16, 1
	v_add3_u32 v3, v4, v3, s2
	v_bfe_u32 v4, v5, 16, 1
	v_lshrrev_b32_e32 v3, 16, v3
	v_add3_u32 v4, v5, v4, s2
	v_and_or_b32 v3, v4, s33, v3
	v_bfe_u32 v4, v8, 16, 1
	v_add3_u32 v4, v8, v4, s2
	v_bfe_u32 v5, v9, 16, 1
	v_lshrrev_b32_e32 v4, 16, v4
	v_add3_u32 v5, v9, v5, s2
	v_and_or_b32 v4, v5, s33, v4
	v_bfe_u32 v5, v10, 16, 1
	v_add3_u32 v5, v10, v5, s2
	v_bfe_u32 v8, v11, 16, 1
	v_lshrrev_b32_e32 v5, 16, v5
	v_add3_u32 v8, v11, v8, s2
	v_or_b32_e32 v12, s6, v1
	v_and_or_b32 v5, v8, s33, v5
	v_lshlrev_b64 v[8:9], 11, v[12:13]
	v_lshl_add_u64 v[6:7], v[6:7], 0, v[8:9]
	global_store_dwordx4 v[6:7], v[2:5], off
	s_waitcnt lgkmcnt(0)
	s_waitcnt lgkmcnt(0)
	s_barrier

.LBB0_2911:
	s_add_u32 s10, s68, 0x7800000
	s_addc_u32 s11, s69, 0
	s_add_u32 s8, s68, 0xb800000
	s_addc_u32 s9, s69, 0
	s_lshl_b32 s4, s6, 8
	s_add_i32 s3, s2, 0x4000
	v_lshl_or_b32 v130, v138, 2, s4
	v_or_b32_e32 v130, s26, v130
	v_or_b32_e32 v134, s3, v1
	s_movk_i32 s4, 0x4080
	s_movk_i32 s12, 0x4000
	s_ashr_i32 s3, s3, 13
	v_cmp_gt_i32_e32 vcc, s4, v134
	v_or_b32_e32 v132, 16, v130
	s_and_saveexec_b64 s[6:7], vcc
	s_cbranch_execz .LBB0_2913
	v_add_u32_e32 v131, 0xffffc002, v134
	v_mov_b32_e32 v133, s3
	v_cmp_gt_i32_e32 vcc, s12, v134
	s_mov_b32 s12, 0x9000
	v_mov_b64_e32 v[136:137], s[42:43]
	v_cndmask_b32_e32 v131, v131, v133, vcc
	v_mad_i64_i32 v[136:137], s[12:13], v131, s12, v[136:137]
	s_mov_b64 s[12:13], 0x5000
	v_ashrrev_i32_e32 v135, 31, v134
	v_lshl_add_u64 v[144:145], v[136:137], 0, s[12:13]
	v_lshlrev_b64 v[136:137], 12, v[134:135]
	v_add_u32_e32 v148, 0xffffc000, v134
	v_mov_b32_e32 v149, 0
	v_lshl_add_u64 v[146:147], s[10:11], 0, v[136:137]
	v_lshlrev_b64 v[136:137], 12, v[148:149]
	v_lshl_add_u64 v[136:137], s[8:9], 0, v[136:137]
	v_mov_b32_e32 v131, v149
	v_cndmask_b32_e32 v141, v137, v147, vcc
	v_cndmask_b32_e32 v140, v136, v146, vcc
	v_lshlrev_b64 v[150:151], 2, v[130:131]
	v_lshl_add_u64 v[136:137], v[144:145], 0, v[150:151]
	v_lshl_add_u64 v[152:153], v[140:141], 0, v[150:151]
	global_load_dwordx4 v[136:139], v[136:137], off
	v_mov_b32_e32 v133, v149
	global_load_dwordx4 v[140:143], v[152:153], off
	v_lshl_add_u64 v[146:147], v[146:147], 0, v[150:151]
	v_lshl_add_u64 v[150:151], v[132:133], 2, v[144:145]
	v_or_b32_e32 v148, 0x80, v130
	s_waitcnt vmcnt(0) lgkmcnt(0)
	v_pk_fma_f32 v[128:129], v[128:129], v[138:139], v[142:143]
	v_pk_fma_f32 v[126:127], v[126:127], v[136:137], v[140:141]
	global_store_dwordx4 v[146:147], v[126:129], off
	global_load_dwordx4 v[126:129], v[150:151], off
	s_nop 0
	global_load_dwordx4 v[136:139], v[152:153], off offset:64
	v_lshl_add_u64 v[140:141], v[148:149], 2, v[144:145]
	v_or_b32_e32 v148, 0x90, v130
	s_waitcnt vmcnt(0) lgkmcnt(0)
	v_pk_fma_f32 v[124:125], v[124:125], v[128:129], v[138:139]
	v_pk_fma_f32 v[122:123], v[122:123], v[126:127], v[136:137]
	global_store_dwordx4 v[146:147], v[122:125], off offset:64
	global_load_dwordx4 v[122:125], v[140:141], off
	s_nop 0
	global_load_dwordx4 v[126:129], v[152:153], off offset:512
	v_lshl_add_u64 v[136:137], v[148:149], 2, v[144:145]
	s_waitcnt vmcnt(0) lgkmcnt(0)
	v_pk_fma_f32 v[120:121], v[120:121], v[124:125], v[128:129]
	v_pk_fma_f32 v[118:119], v[118:119], v[122:123], v[126:127]
	global_store_dwordx4 v[146:147], v[118:121], off offset:512
	global_load_dwordx4 v[118:121], v[136:137], off
	s_nop 0
	global_load_dwordx4 v[122:125], v[152:153], off offset:576
	s_waitcnt vmcnt(0) lgkmcnt(0)
	v_pk_fma_f32 v[116:117], v[116:117], v[120:121], v[124:125]
	v_pk_fma_f32 v[114:115], v[114:115], v[118:119], v[122:123]
	global_store_dwordx4 v[146:147], v[114:117], off offset:576
.LBB0_2913:
	s_or_b64 exec, exec, s[6:7]
	s_nop 0
	v_or_b32_e32 v114, 16, v134
	v_cmp_gt_i32_e32 vcc, s4, v114
	s_and_saveexec_b64 s[6:7], vcc
	s_cbranch_execz .LBB0_2915
	s_movk_i32 s4, 0x4000
	v_add_u32_e32 v115, 0xffffc012, v134
	v_mov_b32_e32 v116, s3
	v_cmp_gt_i32_e32 vcc, s4, v114
	s_mov_b32 s4, 0x9000
	v_add_u32_e32 v126, 0xffffc010, v134
	v_cndmask_b32_e32 v115, v115, v116, vcc
	v_mov_b64_e32 v[116:117], s[42:43]
	v_mad_i64_i32 v[116:117], s[12:13], v115, s4, v[116:117]
	v_ashrrev_i32_e32 v115, 31, v114
	v_lshlrev_b64 v[114:115], 12, v[114:115]
	v_mov_b32_e32 v127, 0
	v_lshl_add_u64 v[124:125], s[10:11], 0, v[114:115]
	v_lshlrev_b64 v[114:115], 12, v[126:127]
	s_mov_b64 s[12:13], 0x5000
	v_lshl_add_u64 v[114:115], s[8:9], 0, v[114:115]
	v_mov_b32_e32 v131, v127
	v_lshl_add_u64 v[122:123], v[116:117], 0, s[12:13]
	v_cndmask_b32_e32 v119, v115, v125, vcc
	v_cndmask_b32_e32 v118, v114, v124, vcc
	v_lshlrev_b64 v[128:129], 2, v[130:131]
	v_lshl_add_u64 v[114:115], v[122:123], 0, v[128:129]
	v_lshl_add_u64 v[136:137], v[118:119], 0, v[128:129]
	global_load_dwordx4 v[114:117], v[114:115], off
	v_mov_b32_e32 v133, v127
	global_load_dwordx4 v[118:121], v[136:137], off
	v_lshl_add_u64 v[124:125], v[124:125], 0, v[128:129]
	v_lshl_add_u64 v[128:129], v[132:133], 2, v[122:123]
	v_or_b32_e32 v126, 0x80, v130
	s_waitcnt vmcnt(0) lgkmcnt(0)
	v_pk_fma_f32 v[112:113], v[112:113], v[116:117], v[120:121]
	v_pk_fma_f32 v[110:111], v[110:111], v[114:115], v[118:119]
	global_store_dwordx4 v[124:125], v[110:113], off
	global_load_dwordx4 v[110:113], v[128:129], off
	s_nop 0
	global_load_dwordx4 v[114:117], v[136:137], off offset:64
	v_lshl_add_u64 v[118:119], v[126:127], 2, v[122:123]
	v_or_b32_e32 v126, 0x90, v130
	s_waitcnt vmcnt(0) lgkmcnt(0)
	v_pk_fma_f32 v[108:109], v[108:109], v[112:113], v[116:117]
	v_pk_fma_f32 v[106:107], v[106:107], v[110:111], v[114:115]
	global_store_dwordx4 v[124:125], v[106:109], off offset:64
	global_load_dwordx4 v[106:109], v[118:119], off
	s_nop 0
	global_load_dwordx4 v[110:113], v[136:137], off offset:512
	v_lshl_add_u64 v[114:115], v[126:127], 2, v[122:123]
	s_waitcnt vmcnt(0) lgkmcnt(0)
	v_pk_fma_f32 v[104:105], v[104:105], v[108:109], v[112:113]
	v_pk_fma_f32 v[102:103], v[102:103], v[106:107], v[110:111]
	global_store_dwordx4 v[124:125], v[102:105], off offset:512
	global_load_dwordx4 v[102:105], v[114:115], off
	s_nop 0
	global_load_dwordx4 v[106:109], v[136:137], off offset:576
	s_waitcnt vmcnt(0) lgkmcnt(0)
	v_pk_fma_f32 v[100:101], v[100:101], v[104:105], v[108:109]
	v_pk_fma_f32 v[98:99], v[98:99], v[102:103], v[106:107]
	global_store_dwordx4 v[124:125], v[98:101], off offset:576
.LBB0_2915:
	s_or_b64 exec, exec, s[6:7]
	s_nop 0
	v_or_b32_e32 v98, 32, v134
	s_movk_i32 s4, 0x4080
	v_cmp_gt_i32_e32 vcc, s4, v98
	s_and_saveexec_b64 s[6:7], vcc
	s_cbranch_execz .LBB0_2917
	s_movk_i32 s12, 0x4000
	v_add_u32_e32 v99, 0xffffc022, v134
	v_mov_b32_e32 v100, s3
	v_cmp_gt_i32_e32 vcc, s12, v98
	s_mov_b32 s12, 0x9000
	v_add_u32_e32 v110, 0xffffc020, v134
	v_cndmask_b32_e32 v99, v99, v100, vcc
	v_mov_b64_e32 v[100:101], s[42:43]
	v_mad_i64_i32 v[100:101], s[12:13], v99, s12, v[100:101]
	v_ashrrev_i32_e32 v99, 31, v98
	v_lshlrev_b64 v[98:99], 12, v[98:99]
	v_mov_b32_e32 v111, 0
	v_lshl_add_u64 v[108:109], s[10:11], 0, v[98:99]
	v_lshlrev_b64 v[98:99], 12, v[110:111]
	s_mov_b64 s[12:13], 0x5000
	v_lshl_add_u64 v[98:99], s[8:9], 0, v[98:99]
	v_mov_b32_e32 v131, v111
	v_lshl_add_u64 v[106:107], v[100:101], 0, s[12:13]
	v_cndmask_b32_e32 v103, v99, v109, vcc
	v_cndmask_b32_e32 v102, v98, v108, vcc
	v_lshlrev_b64 v[112:113], 2, v[130:131]
	v_lshl_add_u64 v[98:99], v[106:107], 0, v[112:113]
	v_lshl_add_u64 v[114:115], v[102:103], 0, v[112:113]
	global_load_dwordx4 v[98:101], v[98:99], off
	v_mov_b32_e32 v133, v111
	global_load_dwordx4 v[102:105], v[114:115], off
	v_lshl_add_u64 v[108:109], v[108:109], 0, v[112:113]
	v_lshl_add_u64 v[112:113], v[132:133], 2, v[106:107]
	v_or_b32_e32 v110, 0x80, v130
	s_waitcnt vmcnt(0) lgkmcnt(0)
	v_pk_fma_f32 v[96:97], v[96:97], v[100:101], v[104:105]
	v_pk_fma_f32 v[94:95], v[94:95], v[98:99], v[102:103]
	global_store_dwordx4 v[108:109], v[94:97], off
	global_load_dwordx4 v[94:97], v[112:113], off
	s_nop 0
	global_load_dwordx4 v[98:101], v[114:115], off offset:64
	v_lshl_add_u64 v[102:103], v[110:111], 2, v[106:107]
	v_or_b32_e32 v110, 0x90, v130
	s_waitcnt vmcnt(0) lgkmcnt(0)
	v_pk_fma_f32 v[92:93], v[92:93], v[96:97], v[100:101]
	v_pk_fma_f32 v[90:91], v[90:91], v[94:95], v[98:99]
	global_store_dwordx4 v[108:109], v[90:93], off offset:64
	global_load_dwordx4 v[90:93], v[102:103], off
	s_nop 0
	global_load_dwordx4 v[94:97], v[114:115], off offset:512
	v_lshl_add_u64 v[98:99], v[110:111], 2, v[106:107]
	s_waitcnt vmcnt(0) lgkmcnt(0)
	v_pk_fma_f32 v[88:89], v[88:89], v[92:93], v[96:97]
	v_pk_fma_f32 v[86:87], v[86:87], v[90:91], v[94:95]
	global_store_dwordx4 v[108:109], v[86:89], off offset:512
	global_load_dwordx4 v[86:89], v[98:99], off
	s_nop 0
	global_load_dwordx4 v[90:93], v[114:115], off offset:576
	s_waitcnt vmcnt(0) lgkmcnt(0)
	v_pk_fma_f32 v[84:85], v[84:85], v[88:89], v[92:93]
	v_pk_fma_f32 v[82:83], v[82:83], v[86:87], v[90:91]
	global_store_dwordx4 v[108:109], v[82:85], off offset:576
.LBB0_2917:
	s_or_b64 exec, exec, s[6:7]
	s_nop 0
	v_or_b32_e32 v82, 48, v134
	v_cmp_gt_i32_e32 vcc, s4, v82
	s_and_saveexec_b64 s[6:7], vcc
	s_cbranch_execz .LBB0_2919
	s_movk_i32 s4, 0x4000
	v_add_u32_e32 v83, 0xffffc032, v134
	v_mov_b32_e32 v84, s3
	v_cmp_gt_i32_e32 vcc, s4, v82
	s_mov_b32 s3, 0x9000
	v_add_u32_e32 v94, 0xffffc030, v134
	v_cndmask_b32_e32 v83, v83, v84, vcc
	v_mov_b64_e32 v[84:85], s[42:43]
	v_mad_i64_i32 v[84:85], s[12:13], v83, s3, v[84:85]
	v_ashrrev_i32_e32 v83, 31, v82
	v_lshlrev_b64 v[82:83], 12, v[82:83]
	v_mov_b32_e32 v95, 0
	v_lshl_add_u64 v[92:93], s[10:11], 0, v[82:83]
	v_lshlrev_b64 v[82:83], 12, v[94:95]
	s_mov_b64 s[12:13], 0x5000
	v_lshl_add_u64 v[82:83], s[8:9], 0, v[82:83]
	v_mov_b32_e32 v131, v95
	v_lshl_add_u64 v[90:91], v[84:85], 0, s[12:13]
	v_cndmask_b32_e32 v87, v83, v93, vcc
	v_cndmask_b32_e32 v86, v82, v92, vcc
	v_lshlrev_b64 v[96:97], 2, v[130:131]
	v_lshl_add_u64 v[82:83], v[90:91], 0, v[96:97]
	v_lshl_add_u64 v[98:99], v[86:87], 0, v[96:97]
	global_load_dwordx4 v[82:85], v[82:83], off
	v_mov_b32_e32 v133, v95
	global_load_dwordx4 v[86:89], v[98:99], off
	v_lshl_add_u64 v[92:93], v[92:93], 0, v[96:97]
	v_lshl_add_u64 v[96:97], v[132:133], 2, v[90:91]
	v_or_b32_e32 v94, 0x80, v130
	s_waitcnt vmcnt(0) lgkmcnt(0)
	v_pk_fma_f32 v[80:81], v[80:81], v[84:85], v[88:89]
	v_pk_fma_f32 v[78:79], v[78:79], v[82:83], v[86:87]
	global_store_dwordx4 v[92:93], v[78:81], off
	global_load_dwordx4 v[78:81], v[96:97], off
	s_nop 0
	global_load_dwordx4 v[82:85], v[98:99], off offset:64
	v_lshl_add_u64 v[86:87], v[94:95], 2, v[90:91]
	v_or_b32_e32 v94, 0x90, v130
	s_waitcnt vmcnt(0) lgkmcnt(0)
	v_pk_fma_f32 v[76:77], v[76:77], v[80:81], v[84:85]
	v_pk_fma_f32 v[74:75], v[74:75], v[78:79], v[82:83]
	global_store_dwordx4 v[92:93], v[74:77], off offset:64
	global_load_dwordx4 v[74:77], v[86:87], off
	s_nop 0
	global_load_dwordx4 v[78:81], v[98:99], off offset:512
	v_lshl_add_u64 v[82:83], v[94:95], 2, v[90:91]
	s_waitcnt vmcnt(0) lgkmcnt(0)
	v_pk_fma_f32 v[72:73], v[72:73], v[76:77], v[80:81]
	v_pk_fma_f32 v[70:71], v[70:71], v[74:75], v[78:79]
	global_store_dwordx4 v[92:93], v[70:73], off offset:512
	global_load_dwordx4 v[70:73], v[82:83], off
	s_nop 0
	global_load_dwordx4 v[74:77], v[98:99], off offset:576
	s_waitcnt vmcnt(0) lgkmcnt(0)
	v_pk_fma_f32 v[68:69], v[68:69], v[72:73], v[76:77]
	v_pk_fma_f32 v[66:67], v[66:67], v[70:71], v[74:75]
	global_store_dwordx4 v[92:93], v[66:69], off offset:576
.LBB0_2919:
	s_or_b64 exec, exec, s[6:7]
	s_addk_i32 s2, 0x4080
	s_movk_i32 s3, 0x4080
	v_or_b32_e32 v66, s2, v1
	s_ashr_i32 s2, s2, 13
	v_cmp_gt_i32_e32 vcc, s3, v66
	s_and_saveexec_b64 s[6:7], vcc
	s_cbranch_execz .LBB0_2921
	s_movk_i32 s4, 0x4000
	v_add_u32_e32 v1, 0xffffc002, v66
	v_mov_b32_e32 v67, s2
	v_cmp_gt_i32_e32 vcc, s4, v66
	s_mov_b32 s4, 0x9000
	v_mov_b64_e32 v[68:69], s[42:43]
	v_cndmask_b32_e32 v1, v1, v67, vcc
	v_mad_i64_i32 v[68:69], s[12:13], v1, s4, v[68:69]
	s_mov_b64 s[12:13], 0x5000
	v_ashrrev_i32_e32 v67, 31, v66
	v_lshl_add_u64 v[76:77], v[68:69], 0, s[12:13]
	v_lshlrev_b64 v[68:69], 12, v[66:67]
	v_add_u32_e32 v80, 0xffffc000, v66
	v_mov_b32_e32 v81, 0
	v_lshl_add_u64 v[78:79], s[10:11], 0, v[68:69]
	v_lshlrev_b64 v[68:69], 12, v[80:81]
	v_lshl_add_u64 v[68:69], s[8:9], 0, v[68:69]
	v_mov_b32_e32 v131, v81
	v_cndmask_b32_e32 v73, v69, v79, vcc
	v_cndmask_b32_e32 v72, v68, v78, vcc
	v_lshlrev_b64 v[82:83], 2, v[130:131]
	v_lshl_add_u64 v[68:69], v[76:77], 0, v[82:83]
	v_lshl_add_u64 v[84:85], v[72:73], 0, v[82:83]
	global_load_dwordx4 v[68:71], v[68:69], off
	v_mov_b32_e32 v133, v81
	global_load_dwordx4 v[72:75], v[84:85], off
	v_lshl_add_u64 v[78:79], v[78:79], 0, v[82:83]
	v_lshl_add_u64 v[82:83], v[132:133], 2, v[76:77]
	v_or_b32_e32 v80, 0x80, v130
	s_waitcnt vmcnt(0) lgkmcnt(0)
	v_pk_fma_f32 v[64:65], v[64:65], v[70:71], v[74:75]
	v_pk_fma_f32 v[62:63], v[62:63], v[68:69], v[72:73]
	global_store_dwordx4 v[78:79], v[62:65], off
	global_load_dwordx4 v[62:65], v[82:83], off
	s_nop 0
	global_load_dwordx4 v[68:71], v[84:85], off offset:64
	v_lshl_add_u64 v[72:73], v[80:81], 2, v[76:77]
	v_or_b32_e32 v80, 0x90, v130
	s_waitcnt vmcnt(0) lgkmcnt(0)
	v_pk_fma_f32 v[60:61], v[60:61], v[64:65], v[70:71]
	v_pk_fma_f32 v[58:59], v[58:59], v[62:63], v[68:69]
	global_store_dwordx4 v[78:79], v[58:61], off offset:64
	global_load_dwordx4 v[58:61], v[72:73], off
	s_nop 0
	global_load_dwordx4 v[62:65], v[84:85], off offset:512
	v_lshl_add_u64 v[68:69], v[80:81], 2, v[76:77]
	s_waitcnt vmcnt(0) lgkmcnt(0)
	v_pk_fma_f32 v[56:57], v[56:57], v[60:61], v[64:65]
	v_pk_fma_f32 v[54:55], v[54:55], v[58:59], v[62:63]
	global_store_dwordx4 v[78:79], v[54:57], off offset:512
	global_load_dwordx4 v[54:57], v[68:69], off
	s_nop 0
	global_load_dwordx4 v[58:61], v[84:85], off offset:576
	s_waitcnt vmcnt(0) lgkmcnt(0)
	v_pk_fma_f32 v[52:53], v[52:53], v[56:57], v[60:61]
	v_pk_fma_f32 v[50:51], v[50:51], v[54:55], v[58:59]
	global_store_dwordx4 v[78:79], v[50:53], off offset:576
.LBB0_2921:
	s_or_b64 exec, exec, s[6:7]
	s_nop 0
	v_or_b32_e32 v50, 16, v66
	v_cmp_gt_i32_e32 vcc, s3, v50
	s_and_saveexec_b64 s[6:7], vcc
	s_cbranch_execz .LBB0_2923
	s_movk_i32 s3, 0x4000
	v_add_u32_e32 v1, 0xffffc012, v66
	v_mov_b32_e32 v51, s2
	v_cmp_gt_i32_e32 vcc, s3, v50
	s_mov_b32 s3, 0x9000
	v_mov_b64_e32 v[52:53], s[42:43]
	v_cndmask_b32_e32 v1, v1, v51, vcc
	v_ashrrev_i32_e32 v51, 31, v50
	v_lshlrev_b64 v[50:51], 12, v[50:51]
	v_add_u32_e32 v62, 0xffffc010, v66
	v_mov_b32_e32 v63, 0
	v_mad_i64_i32 v[52:53], s[12:13], v1, s3, v[52:53]
	v_lshl_add_u64 v[60:61], s[10:11], 0, v[50:51]
	v_lshlrev_b64 v[50:51], 12, v[62:63]
	s_mov_b64 s[12:13], 0x5000
	v_lshl_add_u64 v[50:51], s[8:9], 0, v[50:51]
	v_mov_b32_e32 v131, v63
	v_lshl_add_u64 v[58:59], v[52:53], 0, s[12:13]
	v_cndmask_b32_e32 v55, v51, v61, vcc
	v_cndmask_b32_e32 v54, v50, v60, vcc
	v_lshlrev_b64 v[64:65], 2, v[130:131]
	v_lshl_add_u64 v[50:51], v[58:59], 0, v[64:65]
	v_lshl_add_u64 v[68:69], v[54:55], 0, v[64:65]
	global_load_dwordx4 v[50:53], v[50:51], off
	v_mov_b32_e32 v133, v63
	global_load_dwordx4 v[54:57], v[68:69], off
	v_lshl_add_u64 v[60:61], v[60:61], 0, v[64:65]
	v_lshl_add_u64 v[64:65], v[132:133], 2, v[58:59]
	v_or_b32_e32 v62, 0x80, v130
	s_waitcnt vmcnt(0) lgkmcnt(0)
	v_pk_fma_f32 v[48:49], v[48:49], v[52:53], v[56:57]
	v_pk_fma_f32 v[46:47], v[46:47], v[50:51], v[54:55]
	global_store_dwordx4 v[60:61], v[46:49], off
	global_load_dwordx4 v[46:49], v[64:65], off
	s_nop 0
	global_load_dwordx4 v[50:53], v[68:69], off offset:64
	v_lshl_add_u64 v[54:55], v[62:63], 2, v[58:59]
	v_or_b32_e32 v62, 0x90, v130
	s_waitcnt vmcnt(0) lgkmcnt(0)
	v_pk_fma_f32 v[44:45], v[44:45], v[48:49], v[52:53]
	v_pk_fma_f32 v[42:43], v[42:43], v[46:47], v[50:51]
	global_store_dwordx4 v[60:61], v[42:45], off offset:64
	global_load_dwordx4 v[42:45], v[54:55], off
	s_nop 0
	global_load_dwordx4 v[46:49], v[68:69], off offset:512
	v_lshl_add_u64 v[50:51], v[62:63], 2, v[58:59]
	s_waitcnt vmcnt(0) lgkmcnt(0)
	v_pk_fma_f32 v[40:41], v[40:41], v[44:45], v[48:49]
	v_pk_fma_f32 v[38:39], v[38:39], v[42:43], v[46:47]
	global_store_dwordx4 v[60:61], v[38:41], off offset:512
	global_load_dwordx4 v[38:41], v[50:51], off
	s_nop 0
	global_load_dwordx4 v[42:45], v[68:69], off offset:576
	s_waitcnt vmcnt(0) lgkmcnt(0)
	v_pk_fma_f32 v[36:37], v[36:37], v[40:41], v[44:45]
	v_pk_fma_f32 v[34:35], v[34:35], v[38:39], v[42:43]
	global_store_dwordx4 v[60:61], v[34:37], off offset:576
.LBB0_2923:
	s_or_b64 exec, exec, s[6:7]
	s_nop 0
	v_or_b32_e32 v34, 32, v66
	s_movk_i32 s3, 0x4080
	v_cmp_gt_i32_e32 vcc, s3, v34
	s_and_saveexec_b64 s[6:7], vcc
	s_cbranch_execz .LBB0_2925
	s_movk_i32 s4, 0x4000
	v_add_u32_e32 v1, 0xffffc022, v66
	v_mov_b32_e32 v35, s2
	v_cmp_gt_i32_e32 vcc, s4, v34
	s_mov_b32 s4, 0x9000
	v_mov_b64_e32 v[36:37], s[42:43]
	v_cndmask_b32_e32 v1, v1, v35, vcc
	v_ashrrev_i32_e32 v35, 31, v34
	v_lshlrev_b64 v[34:35], 12, v[34:35]
	v_add_u32_e32 v46, 0xffffc020, v66
	v_mov_b32_e32 v47, 0
	v_mad_i64_i32 v[36:37], s[12:13], v1, s4, v[36:37]
	v_lshl_add_u64 v[44:45], s[10:11], 0, v[34:35]
	v_lshlrev_b64 v[34:35], 12, v[46:47]
	s_mov_b64 s[12:13], 0x5000
	v_lshl_add_u64 v[34:35], s[8:9], 0, v[34:35]
	v_mov_b32_e32 v131, v47
	v_lshl_add_u64 v[42:43], v[36:37], 0, s[12:13]
	v_cndmask_b32_e32 v39, v35, v45, vcc
	v_cndmask_b32_e32 v38, v34, v44, vcc
	v_lshlrev_b64 v[48:49], 2, v[130:131]
	v_lshl_add_u64 v[34:35], v[42:43], 0, v[48:49]
	v_lshl_add_u64 v[50:51], v[38:39], 0, v[48:49]
	global_load_dwordx4 v[34:37], v[34:35], off
	v_mov_b32_e32 v133, v47
	global_load_dwordx4 v[38:41], v[50:51], off
	v_lshl_add_u64 v[44:45], v[44:45], 0, v[48:49]
	v_lshl_add_u64 v[48:49], v[132:133], 2, v[42:43]
	v_or_b32_e32 v46, 0x80, v130
	s_waitcnt vmcnt(0) lgkmcnt(0)
	v_pk_fma_f32 v[32:33], v[32:33], v[36:37], v[40:41]
	v_pk_fma_f32 v[30:31], v[30:31], v[34:35], v[38:39]
	global_store_dwordx4 v[44:45], v[30:33], off
	global_load_dwordx4 v[30:33], v[48:49], off
	s_nop 0
	global_load_dwordx4 v[34:37], v[50:51], off offset:64
	v_lshl_add_u64 v[38:39], v[46:47], 2, v[42:43]
	v_or_b32_e32 v46, 0x90, v130
	s_waitcnt vmcnt(0) lgkmcnt(0)
	v_pk_fma_f32 v[28:29], v[28:29], v[32:33], v[36:37]
	v_pk_fma_f32 v[26:27], v[26:27], v[30:31], v[34:35]
	global_store_dwordx4 v[44:45], v[26:29], off offset:64
	global_load_dwordx4 v[26:29], v[38:39], off
	s_nop 0
	global_load_dwordx4 v[30:33], v[50:51], off offset:512
	v_lshl_add_u64 v[34:35], v[46:47], 2, v[42:43]
	s_waitcnt vmcnt(0) lgkmcnt(0)
	v_pk_fma_f32 v[24:25], v[24:25], v[28:29], v[32:33]
	v_pk_fma_f32 v[22:23], v[22:23], v[26:27], v[30:31]
	global_store_dwordx4 v[44:45], v[22:25], off offset:512
	global_load_dwordx4 v[22:25], v[34:35], off
	s_nop 0
	global_load_dwordx4 v[26:29], v[50:51], off offset:576
	s_waitcnt vmcnt(0) lgkmcnt(0)
	v_pk_fma_f32 v[20:21], v[20:21], v[24:25], v[28:29]
	v_pk_fma_f32 v[18:19], v[18:19], v[22:23], v[26:27]
	global_store_dwordx4 v[44:45], v[18:21], off offset:576
.LBB0_2925:
	s_or_b64 exec, exec, s[6:7]
	s_nop 0
	v_or_b32_e32 v18, 48, v66
	v_cmp_gt_i32_e32 vcc, s3, v18
	s_and_saveexec_b64 s[6:7], vcc
	s_cbranch_execz .LBB0_2927
	s_movk_i32 s3, 0x4000
	v_add_u32_e32 v1, 0xffffc032, v66
	v_mov_b32_e32 v19, s2
	v_cmp_gt_i32_e32 vcc, s3, v18
	s_mov_b32 s2, 0x9000
	v_mov_b64_e32 v[20:21], s[42:43]
	v_cndmask_b32_e32 v1, v1, v19, vcc
	v_ashrrev_i32_e32 v19, 31, v18
	v_lshlrev_b64 v[18:19], 12, v[18:19]
	v_add_u32_e32 v30, 0xffffc030, v66
	v_mov_b32_e32 v31, 0
	v_mad_i64_i32 v[20:21], s[2:3], v1, s2, v[20:21]
	v_lshl_add_u64 v[28:29], s[10:11], 0, v[18:19]
	v_lshlrev_b64 v[18:19], 12, v[30:31]
	s_mov_b64 s[2:3], 0x5000
	v_lshl_add_u64 v[18:19], s[8:9], 0, v[18:19]
	v_mov_b32_e32 v131, v31
	v_lshl_add_u64 v[26:27], v[20:21], 0, s[2:3]
	v_cndmask_b32_e32 v23, v19, v29, vcc
	v_cndmask_b32_e32 v22, v18, v28, vcc
	v_lshlrev_b64 v[32:33], 2, v[130:131]
	v_lshl_add_u64 v[18:19], v[26:27], 0, v[32:33]
	v_lshl_add_u64 v[34:35], v[22:23], 0, v[32:33]
	global_load_dwordx4 v[18:21], v[18:19], off
	v_mov_b32_e32 v133, v31
	global_load_dwordx4 v[22:25], v[34:35], off
	v_lshl_add_u64 v[28:29], v[28:29], 0, v[32:33]
	v_lshl_add_u64 v[32:33], v[132:133], 2, v[26:27]
	v_or_b32_e32 v30, 0x80, v130
	s_waitcnt vmcnt(0) lgkmcnt(0)
	v_pk_fma_f32 v[16:17], v[16:17], v[20:21], v[24:25]
	v_pk_fma_f32 v[14:15], v[14:15], v[18:19], v[22:23]
	global_store_dwordx4 v[28:29], v[14:17], off
	global_load_dwordx4 v[14:17], v[32:33], off
	s_nop 0
	global_load_dwordx4 v[18:21], v[34:35], off offset:64
	v_lshl_add_u64 v[22:23], v[30:31], 2, v[26:27]
	v_or_b32_e32 v30, 0x90, v130
	s_waitcnt vmcnt(0) lgkmcnt(0)
	v_pk_fma_f32 v[12:13], v[12:13], v[16:17], v[20:21]
	v_pk_fma_f32 v[10:11], v[10:11], v[14:15], v[18:19]
	global_store_dwordx4 v[28:29], v[10:13], off offset:64
	global_load_dwordx4 v[10:13], v[22:23], off
	s_nop 0
	global_load_dwordx4 v[14:17], v[34:35], off offset:512
	v_lshl_add_u64 v[18:19], v[30:31], 2, v[26:27]
	s_waitcnt vmcnt(0) lgkmcnt(0)
	v_pk_fma_f32 v[8:9], v[8:9], v[12:13], v[16:17]
	v_pk_fma_f32 v[6:7], v[6:7], v[10:11], v[14:15]
	global_store_dwordx4 v[28:29], v[6:9], off offset:512
	global_load_dwordx4 v[6:9], v[18:19], off
	s_nop 0
	global_load_dwordx4 v[10:13], v[34:35], off offset:576
	s_waitcnt vmcnt(0) lgkmcnt(0)
	v_pk_fma_f32 v[4:5], v[4:5], v[8:9], v[12:13]
	v_pk_fma_f32 v[2:3], v[2:3], v[6:7], v[10:11]
	global_store_dwordx4 v[28:29], v[2:5], off offset:576

.LBB0_2935:
	s_or_b64 exec, exec, s[6:7]
	v_mov_b32_e32 v1, v0
	v_mov_b64_e32 v[2:3], s[0:1]
	s_barrier
	global_load_dwordx2 v[2:3], v[2:3], off offset:88 sc0 sc1
	s_waitcnt vmcnt(0)
	v_readfirstlane_b32 s2, v1
	s_ashr_i32 s2, s2, 4
	s_and_b32 s3, s2, -4
	s_cmp_gt_i32 s3, 31
	s_cbranch_scc1 .LBB0_2938
	v_and_b32_e32 v21, 63, v1
	v_mov_b32_e32 v91, 0
	v_lshlrev_b32_e32 v90, 4, v21
	s_waitcnt lgkmcnt(0)
	v_lshl_add_u64 v[2:3], v[2:3], 0, v[90:91]
	s_movk_i32 s2, 0x2000
	v_add_co_u32_e32 v18, vcc, s2, v2
	v_and_b32_e32 v1, 64, v166
	s_nop 0
	v_addc_co_u32_e32 v19, vcc, 0, v3, vcc
	global_load_dwordx4 v[2:5], v[18:19], off
	global_load_dwordx4 v[6:9], v[18:19], off offset:1024
	global_load_dwordx4 v[10:13], v[18:19], off offset:2048
	global_load_dwordx4 v[14:17], v[18:19], off offset:3072
	v_add_u32_e32 v18, 64, v1
	v_xor_b32_e32 v1, 1, v166
	v_cmp_lt_i32_e32 vcc, v1, v18
	v_xor_b32_e32 v19, 2, v166
	s_lshl_b32 s4, s40, 5
	v_cndmask_b32_e32 v1, v166, v1, vcc
	v_cmp_lt_i32_e32 vcc, v19, v18
	s_add_i32 s3, s4, s3
	s_add_i32 s2, s4, 0x20a0
	v_cndmask_b32_e32 v19, v166, v19, vcc
	v_lshlrev_b32_e32 v167, 2, v19
	v_xor_b32_e32 v19, 4, v166
	v_cmp_lt_i32_e32 vcc, v19, v18
	s_add_i32 s12, s3, 0x2080
	s_add_u32 s3, s68, 0x5800000
	v_cndmask_b32_e32 v19, v166, v19, vcc
	v_lshlrev_b32_e32 v168, 2, v19
	v_xor_b32_e32 v19, 8, v166
	v_cmp_lt_i32_e32 vcc, v19, v18
	s_addc_u32 s4, s69, 0
	s_ashr_i32 s13, s12, 31
	v_cndmask_b32_e32 v19, v166, v19, vcc
	v_lshlrev_b32_e32 v169, 2, v19
	v_xor_b32_e32 v19, 16, v166
	v_cmp_lt_i32_e32 vcc, v19, v18
	s_lshl_b64 s[6:7], s[12:13], 11
	v_lshl_or_b32 v92, v21, 3, s6
	v_cndmask_b32_e32 v19, v166, v19, vcc
	v_lshlrev_b32_e32 v170, 2, v19
	v_xor_b32_e32 v19, 32, v166
	v_cmp_lt_i32_e32 vcc, v19, v18
	v_mov_b32_e32 v93, s7
	s_lshl_b64 s[6:7], s[12:13], 12
	v_cndmask_b32_e32 v18, v166, v19, vcc
	v_lshlrev_b32_e32 v171, 2, v18
	v_lshlrev_b32_e32 v18, 2, v21
	v_or_b32_e32 v20, 0x100, v18
	v_or_b32_e32 v22, 0x200, v18
	v_or_b32_e32 v24, 0x300, v18
	v_lshlrev_b32_e32 v1, 2, v1
	v_or_b32_e32 v94, s6, v90
	v_mov_b32_e32 v95, s7
	v_mov_b32_e32 v172, 0x358637bd
	s_mov_b32 s13, 0xf800000
	v_mov_b32_e32 v173, 0x260
	v_lshlrev_b32_e32 v90, 2, v18
	s_movk_i32 s22, 0x7fff
	s_mov_b32 s23, 0xffff0000
	s_mov_b32 s24, 0xba00000
	v_lshlrev_b32_e32 v96, 2, v20
	v_lshlrev_b32_e32 v98, 2, v22
	v_mov_b32_e32 v99, v91
	v_lshlrev_b32_e32 v100, 2, v24
	v_mov_b32_e32 v101, v91
	s_mov_b32 s25, 0xba01000
	s_mov_b64 s[14:15], 0x10000
	s_mov_b64 s[16:17], 0x20000
	v_mov_b32_e32 v97, v91
.LBB0_2937:
	v_lshl_add_u64 v[18:19], s[68:69], 0, v[94:95]
	v_lshl_add_u64 v[22:23], s[68:69], 0, v[92:93]
	v_add_co_u32_e32 v20, vcc, 0x7800000, v18
	v_add_co_u32_e64 v102, s[6:7], s24, v22
	s_nop 0
	v_addc_co_u32_e32 v21, vcc, 0, v19, vcc
	v_addc_co_u32_e64 v103, s[6:7], 0, v23, s[6:7]
	v_add_co_u32_e64 v104, s[6:7], s25, v22
	v_add_co_u32_e32 v22, vcc, 0x7801000, v18
	s_nop 0
	v_addc_co_u32_e64 v105, s[6:7], 0, v23, s[6:7]
	global_load_dwordx4 v[78:81], v[20:21], off
	global_load_dwordx4 v[74:77], v[20:21], off offset:1024
	global_load_dwordx4 v[70:73], v[20:21], off offset:2048
	global_load_dwordx4 v[66:69], v[20:21], off offset:3072
	v_addc_co_u32_e32 v23, vcc, 0, v19, vcc
	v_add_co_u32_e32 v20, vcc, 0x7802000, v18
	global_load_dwordx4 v[62:65], v[22:23], off
	global_load_dwordx4 v[58:61], v[22:23], off offset:1024
	global_load_dwordx4 v[54:57], v[22:23], off offset:2048
	global_load_dwordx4 v[50:53], v[22:23], off offset:3072
	v_addc_co_u32_e32 v21, vcc, 0, v19, vcc
	v_add_co_u32_e32 v82, vcc, 0x7803000, v18
	global_load_dwordx4 v[46:49], v[20:21], off
	global_load_dwordx4 v[42:45], v[20:21], off offset:1024
	global_load_dwordx4 v[38:41], v[20:21], off offset:2048
	global_load_dwordx4 v[34:37], v[20:21], off offset:3072
	v_addc_co_u32_e32 v83, vcc, 0, v19, vcc
	global_load_dwordx4 v[30:33], v[82:83], off
	global_load_dwordx4 v[26:29], v[82:83], off offset:1024
	global_load_dwordx4 v[22:25], v[82:83], off offset:2048
	global_load_dwordx4 v[18:21], v[82:83], off offset:3072
	s_ashr_i32 s8, s12, 13
	s_add_i32 s9, s12, 0xffffc002
	s_cmpk_lt_i32 s12, 0x4000
	s_cselect_b32 s6, s8, s9
	s_mul_hi_i32 s7, s6, 0x9000
	s_mul_i32 s6, s6, 0x9000
	s_add_u32 s9, s3, s6
	s_addc_u32 s11, s4, s7
	s_add_u32 s6, s9, 0x6000
	s_addc_u32 s7, s11, 0
	s_add_u32 s10, s9, 0x7000
	s_addc_u32 s11, s11, 0
	v_lshl_add_u64 v[82:83], s[6:7], 0, v[90:91]
	v_lshl_add_u64 v[86:87], s[10:11], 0, v[90:91]
	global_load_dwordx4 v[82:85], v[82:83], off
	v_lshl_add_u64 v[148:149], s[6:7], 0, v[96:97]
	global_load_dwordx4 v[86:89], v[86:87], off
	v_lshl_add_u64 v[142:143], s[6:7], 0, v[98:99]
	v_lshl_add_u64 v[134:135], s[6:7], 0, v[100:101]
	s_add_i32 s6, s12, 0xffffc003
	s_cmpk_lt_i32 s12, 0x3fff
	s_cselect_b32 s6, s8, s6
	s_mul_hi_i32 s7, s6, 0x9000
	s_mul_i32 s6, s6, 0x9000
	s_add_u32 s9, s3, s6
	v_lshl_add_u64 v[152:153], s[10:11], 0, v[96:97]
	v_lshl_add_u64 v[146:147], s[10:11], 0, v[98:99]
	v_lshl_add_u64 v[140:141], s[10:11], 0, v[100:101]
	s_addc_u32 s11, s4, s7
	s_add_u32 s6, s9, 0x6000
	s_addc_u32 s7, s11, 0
	s_add_u32 s10, s9, 0x7000
	v_lshl_add_u64 v[132:133], s[6:7], 0, v[90:91]
	v_lshl_add_u64 v[126:127], s[6:7], 0, v[96:97]
	v_lshl_add_u64 v[118:119], s[6:7], 0, v[98:99]
	v_lshl_add_u64 v[114:115], s[6:7], 0, v[100:101]
	s_addc_u32 s11, s11, 0
	s_add_i32 s6, s12, 0xffffc004
	s_cmpk_lt_i32 s12, 0x3ffe
	s_cselect_b32 s6, s8, s6
	s_mul_hi_i32 s7, s6, 0x9000
	s_mul_i32 s6, s6, 0x9000
	s_add_u32 s6, s3, s6
	s_addc_u32 s7, s4, s7
	v_lshl_add_u64 v[138:139], s[10:11], 0, v[90:91]
	v_lshl_add_u64 v[130:131], s[10:11], 0, v[96:97]
	v_lshl_add_u64 v[122:123], s[10:11], 0, v[98:99]
	v_lshl_add_u64 v[116:117], s[10:11], 0, v[100:101]
	s_add_u32 s10, s6, 0x6000
	s_addc_u32 s11, s7, 0
	s_add_u32 s6, s6, 0x7000
	s_addc_u32 s7, s7, 0
	s_add_i32 s9, s12, 0xffffc005
	s_cmpk_lt_i32 s12, 0x3ffd
	v_lshl_add_u64 v[156:157], s[6:7], 0, v[90:91]
	v_lshl_add_u64 v[154:155], s[6:7], 0, v[96:97]
	v_lshl_add_u64 v[150:151], s[6:7], 0, v[98:99]
	v_lshl_add_u64 v[136:137], s[6:7], 0, v[100:101]
	s_cselect_b32 s6, s8, s9
	s_mul_hi_i32 s7, s6, 0x9000
	s_mul_i32 s6, s6, 0x9000
	s_add_u32 s6, s3, s6
	s_addc_u32 s7, s4, s7
	s_waitcnt vmcnt(0) lgkmcnt(0)
	v_pk_mul_f32 v[158:159], v[80:81], v[80:81]
	v_pk_mul_f32 v[160:161], v[78:79], v[78:79]
	v_pk_mul_f32 v[162:163], v[76:77], v[76:77]
	v_pk_mul_f32 v[164:165], v[74:75], v[74:75]
	v_mul_f32_e32 v174, v71, v71
	v_mul_f32_e32 v176, v73, v73
	v_mul_f32_e32 v187, v68, v68
	v_mul_f32_e32 v189, v69, v69
	v_pk_mov_b32 v[178:179], v[160:161], v[158:159] op_sel:[1,0]
	v_mov_b32_e32 v161, v159
	v_pk_mov_b32 v[158:159], v[164:165], v[162:163] op_sel:[1,0]
	v_mov_b32_e32 v165, v163
	v_pk_fma_f32 v[162:163], v[70:71], v[70:71], v[174:175] op_sel_hi:[1,1,0]
	v_pk_fma_f32 v[174:175], v[72:73], v[72:73], v[176:177] op_sel_hi:[1,1,0]
	v_pk_mul_f32 v[176:177], v[64:65], v[64:65]
	v_pk_mul_f32 v[180:181], v[62:63], v[62:63]
	v_pk_mul_f32 v[182:183], v[60:61], v[60:61]
	v_pk_mul_f32 v[184:185], v[58:59], v[58:59]
	v_mul_f32_e32 v186, v55, v55
	v_mul_f32_e32 v188, v57, v57
	v_pk_add_f32 v[160:161], v[178:179], v[160:161]
	v_pk_add_f32 v[158:159], v[158:159], v[164:165]
	v_mov_b32_e32 v163, v187
	v_mov_b32_e32 v175, v189
	v_pk_mov_b32 v[164:165], v[180:181], v[176:177] op_sel:[1,0]
	v_mov_b32_e32 v181, v177
	v_pk_mov_b32 v[176:177], v[184:185], v[182:183] op_sel:[1,0]
	v_mov_b32_e32 v185, v183
	v_pk_fma_f32 v[178:179], v[54:55], v[54:55], v[186:187] op_sel_hi:[1,1,0]
	v_pk_fma_f32 v[182:183], v[56:57], v[56:57], v[188:189] op_sel_hi:[1,1,0]
	v_pk_mul_f32 v[186:187], v[48:49], v[48:49]
	v_pk_mul_f32 v[188:189], v[46:47], v[46:47]
	v_pk_mul_f32 v[190:191], v[44:45], v[44:45]
	v_pk_mul_f32 v[192:193], v[42:43], v[42:43]
	v_mul_f32_e32 v197, v66, v66
	v_mul_f32_e32 v203, v67, v67
	v_mul_f32_e32 v195, v52, v52
	v_mul_f32_e32 v202, v53, v53
	v_mul_f32_e32 v194, v39, v39
	v_mul_f32_e32 v196, v41, v41
	v_pk_add_f32 v[198:199], v[160:161], v[160:161] op_sel:[0,1] op_sel_hi:[1,0]
	v_pk_add_f32 v[200:201], v[158:159], v[158:159] op_sel:[0,1] op_sel_hi:[1,0]
	v_pk_add_f32 v[174:175], v[162:163], v[174:175]
	v_pk_add_f32 v[158:159], v[164:165], v[180:181]
	v_pk_add_f32 v[160:161], v[176:177], v[184:185]
	v_pk_mov_b32 v[162:163], v[188:189], v[186:187] op_sel:[1,0]
	v_mov_b32_e32 v189, v187
	v_pk_mov_b32 v[164:165], v[192:193], v[190:191] op_sel:[1,0]
	v_mov_b32_e32 v193, v191
	v_mul_f32_e32 v208, v50, v50
	v_mul_f32_e32 v209, v51, v51
	v_mul_f32_e32 v212, v36, v36
	v_mul_f32_e32 v213, v37, v37
	v_mov_b32_e32 v179, v195
	v_mov_b32_e32 v183, v202
	v_pk_fma_f32 v[176:177], v[38:39], v[38:39], v[194:195] op_sel_hi:[1,1,0]
	v_pk_fma_f32 v[180:181], v[40:41], v[40:41], v[196:197] op_sel_hi:[1,1,0]
	v_pk_mul_f32 v[184:185], v[32:33], v[32:33]
	v_pk_mul_f32 v[186:187], v[30:31], v[30:31]
	v_pk_mul_f32 v[190:191], v[28:29], v[28:29]
	v_pk_mul_f32 v[194:195], v[26:27], v[26:27]
	v_mov_b32_e32 v199, v197
	v_mov_b32_e32 v201, v203
	v_pk_add_f32 v[204:205], v[158:159], v[158:159] op_sel:[0,1] op_sel_hi:[1,0]
	v_pk_add_f32 v[206:207], v[160:161], v[160:161] op_sel:[0,1] op_sel_hi:[1,0]
	v_pk_add_f32 v[162:163], v[162:163], v[188:189]
	v_pk_add_f32 v[164:165], v[164:165], v[192:193]
	v_mul_f32_e32 v210, v34, v34
	v_mul_f32_e32 v211, v35, v35
	v_pk_add_f32 v[178:179], v[178:179], v[182:183]
	v_mov_b32_e32 v177, v212
	v_mov_b32_e32 v181, v213
	v_pk_mov_b32 v[182:183], v[186:187], v[184:185] op_sel:[1,0]
	v_mov_b32_e32 v187, v185
	v_pk_mov_b32 v[184:185], v[194:195], v[190:191] op_sel:[1,0]
	v_mov_b32_e32 v195, v191
	v_pk_add_f32 v[188:189], v[198:199], v[200:201]
	v_mov_b32_e32 v205, v208
	v_mov_b32_e32 v207, v209
	v_pk_add_f32 v[190:191], v[162:163], v[162:163] op_sel:[0,1] op_sel_hi:[1,0]
	v_pk_add_f32 v[192:193], v[164:165], v[164:165] op_sel:[0,1] op_sel_hi:[1,0]
	v_pk_add_f32 v[176:177], v[176:177], v[180:181]
	v_pk_add_f32 v[174:175], v[188:189], v[174:175]
	v_pk_add_f32 v[180:181], v[204:205], v[206:207]
	v_mov_b32_e32 v191, v210
	v_mov_b32_e32 v193, v211
	v_pk_add_f32 v[162:163], v[182:183], v[186:187]
	v_add_f32_e32 v182, v174, v175
	v_pk_add_f32 v[174:175], v[180:181], v[178:179]
	v_pk_add_f32 v[178:179], v[190:191], v[192:193]
	v_add_f32_e32 v180, v174, v175
	v_pk_add_f32 v[174:175], v[178:179], v[176:177]
	ds_bpermute_b32 v176, v1, v182
	ds_bpermute_b32 v177, v1, v180
	v_add_f32_e32 v174, v174, v175
	ds_bpermute_b32 v175, v1, v174
	s_add_u32 s18, s6, 0x6000
	s_waitcnt lgkmcnt(2)
	v_add_f32_e32 v176, v182, v176
	ds_bpermute_b32 v178, v167, v176
	s_waitcnt lgkmcnt(2)
	v_add_f32_e32 v177, v180, v177
	ds_bpermute_b32 v179, v167, v177
	s_waitcnt lgkmcnt(2)
	v_add_f32_e32 v174, v174, v175
	ds_bpermute_b32 v175, v167, v174
	s_waitcnt lgkmcnt(2)
	v_add_f32_e32 v176, v176, v178
	ds_bpermute_b32 v178, v168, v176
	s_waitcnt lgkmcnt(2)
	v_add_f32_e32 v177, v177, v179
	ds_bpermute_b32 v179, v168, v177
	s_waitcnt lgkmcnt(2)
	v_add_f32_e32 v174, v174, v175
	ds_bpermute_b32 v175, v168, v174
	s_waitcnt lgkmcnt(2)
	v_add_f32_e32 v176, v176, v178
	ds_bpermute_b32 v178, v169, v176
	s_waitcnt lgkmcnt(2)
	v_add_f32_e32 v177, v177, v179
	ds_bpermute_b32 v179, v169, v177
	s_waitcnt lgkmcnt(2)
	v_add_f32_e32 v174, v174, v175
	ds_bpermute_b32 v175, v169, v174
	s_waitcnt lgkmcnt(2)
	v_add_f32_e32 v176, v176, v178
	ds_bpermute_b32 v178, v170, v176
	s_waitcnt lgkmcnt(2)
	v_add_f32_e32 v177, v177, v179
	ds_bpermute_b32 v179, v170, v177
	s_waitcnt lgkmcnt(2)
	v_add_f32_e32 v174, v174, v175
	ds_bpermute_b32 v175, v170, v174
	s_waitcnt lgkmcnt(2)
	v_add_f32_e32 v176, v176, v178
	ds_bpermute_b32 v178, v171, v176
	s_waitcnt lgkmcnt(2)
	v_add_f32_e32 v177, v177, v179
	ds_bpermute_b32 v179, v171, v177
	s_waitcnt lgkmcnt(2)
	v_add_f32_e32 v174, v174, v175
	ds_bpermute_b32 v175, v171, v174
	s_waitcnt lgkmcnt(2)
	v_add_f32_e32 v176, v176, v178
	v_fmamk_f32 v176, v176, 0x3a800000, v172
	s_addc_u32 s19, s7, 0
	s_waitcnt lgkmcnt(1)
	v_add_f32_e32 v177, v177, v179
	v_mul_f32_e32 v178, 0x4f800000, v176
	v_cmp_gt_f32_e32 vcc, s13, v176
	s_add_u32 s20, s6, 0x7000
	v_fmamk_f32 v177, v177, 0x3a800000, v172
	s_waitcnt lgkmcnt(0)
	v_add_f32_e32 v174, v174, v175
	v_cndmask_b32_e32 v175, v176, v178, vcc
	s_addc_u32 s21, s7, 0
	v_mul_f32_e32 v176, 0x4f800000, v177
	v_cmp_gt_f32_e64 s[6:7], s13, v177
	v_sqrt_f32_e32 v178, v175
	v_fmamk_f32 v174, v174, 0x3a800000, v172
	v_cndmask_b32_e64 v176, v177, v176, s[6:7]
	v_mul_f32_e32 v177, 0x4f800000, v174
	v_cmp_gt_f32_e64 s[8:9], s13, v174
	v_sqrt_f32_e32 v179, v176
	v_add_u32_e32 v180, -1, v178
	v_cndmask_b32_e64 v174, v174, v177, s[8:9]
	v_sqrt_f32_e32 v177, v174
	v_add_u32_e32 v181, 1, v178
	v_fma_f32 v182, -v180, v178, v175
	v_lshl_add_u64 v[112:113], s[10:11], 0, v[90:91]
	v_lshl_add_u64 v[106:107], s[10:11], 0, v[96:97]
	v_lshl_add_u64 v[110:111], s[10:11], 0, v[98:99]
	v_lshl_add_u64 v[108:109], s[10:11], 0, v[100:101]
	v_pk_add_f32 v[164:165], v[184:185], v[194:195]
	v_fma_f32 v183, -v181, v178, v175
	v_add_u32_e32 v184, -1, v179
	v_cmp_ge_f32_e64 s[10:11], 0, v182
	v_add_u32_e32 v185, 1, v179
	v_fma_f32 v182, -v185, v179, v176
	v_cndmask_b32_e64 v178, v178, v180, s[10:11]
	v_fma_f32 v180, -v184, v179, v176
	v_cmp_lt_f32_e64 s[10:11], 0, v183
	v_add_u32_e32 v186, -1, v177
	v_add_u32_e32 v187, 1, v177
	v_cndmask_b32_e64 v178, v178, v181, s[10:11]
	v_cmp_ge_f32_e64 s[10:11], 0, v180
	v_fma_f32 v180, -v186, v177, v174
	v_fma_f32 v181, -v187, v177, v174
	v_cndmask_b32_e64 v179, v179, v184, s[10:11]
	v_cmp_lt_f32_e64 s[10:11], 0, v182
	v_mul_f32_e32 v182, 0x37800000, v178
	v_cndmask_b32_e32 v178, v178, v182, vcc
	v_cndmask_b32_e64 v179, v179, v185, s[10:11]
	v_cmp_ge_f32_e64 s[10:11], 0, v180
	v_mul_f32_e32 v180, 0x37800000, v179
	v_cmp_class_f32_e32 vcc, v175, v173
	v_cndmask_b32_e64 v177, v177, v186, s[10:11]
	v_cmp_lt_f32_e64 s[10:11], 0, v181
	v_cndmask_b32_e32 v175, v178, v175, vcc
	v_cndmask_b32_e64 v178, v179, v180, s[6:7]
	v_cndmask_b32_e64 v177, v177, v187, s[10:11]
	v_cmp_class_f32_e32 vcc, v176, v173
	v_mul_f32_e32 v179, 0x37800000, v177
	v_div_scale_f32 v180, s[6:7], v175, v175, 1.0
	v_cndmask_b32_e32 v176, v178, v176, vcc
	v_cndmask_b32_e64 v177, v177, v179, s[8:9]
	v_cmp_class_f32_e32 vcc, v174, v173
	v_rcp_f32_e32 v178, v180
	v_div_scale_f32 v179, s[8:9], v176, v176, 1.0
	v_cndmask_b32_e32 v177, v177, v174, vcc
	v_rcp_f32_e32 v183, v179
	v_div_scale_f32 v184, s[10:11], v177, v177, 1.0
	v_rcp_f32_e32 v186, v184
	v_fma_f32 v174, -v180, v178, 1.0
	v_div_scale_f32 v181, s[6:7], 1.0, v175, 1.0
	v_fmac_f32_e32 v178, v174, v178
	v_fma_f32 v174, -v179, v183, 1.0
	v_div_scale_f32 v182, s[8:9], 1.0, v176, 1.0
	v_mul_f32_e32 v187, v181, v178
	v_fmac_f32_e32 v183, v174, v183
	v_fma_f32 v174, -v184, v186, 1.0
	v_fma_f32 v188, -v180, v187, v181
	v_mul_f32_e32 v189, v182, v183
	v_div_scale_f32 v185, s[10:11], 1.0, v177, 1.0
	v_fmac_f32_e32 v186, v174, v186
	v_fmac_f32_e32 v187, v188, v178
	v_fma_f32 v174, -v179, v189, v182
	v_mul_f32_e32 v188, v185, v186
	v_fma_f32 v180, -v180, v187, v181
	v_fmac_f32_e32 v189, v174, v183
	s_mov_b64 vcc, s[6:7]
	v_fma_f32 v174, -v184, v188, v185
	v_div_fmas_f32 v178, v180, v178, v187
	v_fma_f32 v179, -v179, v189, v182
	s_mov_b64 vcc, s[8:9]
	v_fmac_f32_e32 v188, v174, v186
	v_div_fixup_f32 v174, v178, v175, 1.0
	v_div_fmas_f32 v175, v179, v183, v189
	v_fma_f32 v178, -v184, v188, v185
	v_pk_mul_f32 v[80:81], v[80:81], v[174:175] op_sel_hi:[1,0]
	v_pk_mul_f32 v[78:79], v[78:79], v[174:175] op_sel_hi:[1,0]
	s_mov_b64 vcc, s[10:11]
	v_pk_add_f32 v[88:89], v[88:89], 1.0 op_sel_hi:[1,0]
	v_pk_add_f32 v[86:87], v[86:87], 1.0 op_sel_hi:[1,0]
	v_pk_mul_f32 v[76:77], v[76:77], v[174:175] op_sel_hi:[1,0]
	v_pk_mul_f32 v[74:75], v[74:75], v[174:175] op_sel_hi:[1,0]
	v_pk_mul_f32 v[72:73], v[72:73], v[174:175] op_sel_hi:[1,0]
	v_pk_mul_f32 v[70:71], v[70:71], v[174:175] op_sel_hi:[1,0]
	v_pk_mul_f32 v[68:69], v[68:69], v[174:175] op_sel_hi:[1,0]
	v_pk_mul_f32 v[66:67], v[66:67], v[174:175] op_sel_hi:[1,0]
	v_div_fixup_f32 v174, v175, v176, 1.0
	v_div_fmas_f32 v176, v178, v186, v188
	v_pk_mul_f32 v[78:79], v[2:3], v[78:79]
	v_pk_mul_f32 v[80:81], v[4:5], v[80:81]
	v_pk_mul_f32 v[64:65], v[64:65], v[174:175] op_sel_hi:[1,0]
	v_pk_mul_f32 v[62:63], v[62:63], v[174:175] op_sel_hi:[1,0]
	v_pk_mul_f32 v[60:61], v[60:61], v[174:175] op_sel_hi:[1,0]
	v_pk_mul_f32 v[58:59], v[58:59], v[174:175] op_sel_hi:[1,0]
	v_pk_mul_f32 v[56:57], v[56:57], v[174:175] op_sel_hi:[1,0]
	v_pk_mul_f32 v[54:55], v[54:55], v[174:175] op_sel_hi:[1,0]
	v_pk_mul_f32 v[52:53], v[52:53], v[174:175] op_sel_hi:[1,0]
	v_pk_mul_f32 v[174:175], v[50:51], v[174:175] op_sel_hi:[1,0]
	v_div_fixup_f32 v50, v176, v177, 1.0
	v_pk_fma_f32 v[80:81], v[88:89], v[80:81], v[84:85]
	v_pk_fma_f32 v[78:79], v[86:87], v[78:79], v[82:83]
	v_pk_mul_f32 v[86:87], v[16:17], v[52:53]
	v_pk_mul_f32 v[48:49], v[48:49], v[50:51] op_sel_hi:[1,0]
	v_pk_mul_f32 v[46:47], v[46:47], v[50:51] op_sel_hi:[1,0]
	v_bfe_u32 v51, v78, 16, 1
	v_bfe_u32 v53, v80, 16, 1
	v_pk_mul_f32 v[82:83], v[10:11], v[54:55]
	v_pk_mul_f32 v[84:85], v[14:15], v[174:175]
	v_bfe_u32 v52, v79, 16, 1
	v_bfe_u32 v54, v81, 16, 1
	v_pk_mul_f32 v[88:89], v[2:3], v[46:47]
	v_pk_mul_f32 v[174:175], v[4:5], v[48:49]
	v_add3_u32 v46, v78, v51, s22
	v_add3_u32 v48, v80, v53, s22
	v_add3_u32 v47, v79, v52, s22
	v_add3_u32 v49, v81, v54, s22
	v_lshrrev_b32_e32 v46, 16, v46
	v_lshrrev_b32_e32 v48, 16, v48
	v_and_or_b32 v46, v47, s23, v46
	v_and_or_b32 v47, v49, s23, v48
	global_store_dwordx2 v[102:103], v[46:47], off
	global_load_dwordx4 v[46:49], v[152:153], off
	s_nop 0
	global_load_dwordx4 v[52:55], v[148:149], off
	v_pk_mul_f32 v[74:75], v[6:7], v[74:75]
	v_pk_mul_f32 v[76:77], v[8:9], v[76:77]
	v_pk_mul_f32 v[70:71], v[10:11], v[70:71]
	v_pk_mul_f32 v[72:73], v[12:13], v[72:73]
	v_pk_mul_f32 v[66:67], v[66:67], v[14:15]
	v_pk_mul_f32 v[68:69], v[68:69], v[16:17]
	v_pk_mul_f32 v[62:63], v[2:3], v[62:63]
	v_pk_mul_f32 v[64:65], v[4:5], v[64:65]
	v_pk_mul_f32 v[58:59], v[6:7], v[58:59]
	v_pk_mul_f32 v[60:61], v[8:9], v[60:61]
	v_pk_mul_f32 v[56:57], v[12:13], v[56:57]
	v_mul_f32_e32 v196, v23, v23
	v_mul_f32_e32 v202, v25, v25
	v_mul_f32_e32 v214, v18, v18
	v_mul_f32_e32 v215, v19, v19
	v_mul_f32_e32 v216, v20, v20
	v_mul_f32_e32 v217, v21, v21
	v_pk_fma_f32 v[158:159], v[22:23], v[22:23], v[196:197] op_sel_hi:[1,1,0]
	v_pk_fma_f32 v[160:161], v[24:25], v[24:25], v[202:203] op_sel_hi:[1,1,0]
	v_mov_b32_e32 v159, v216
	v_mov_b32_e32 v161, v217
	v_lshl_add_u64 v[144:145], s[20:21], 0, v[90:91]
	v_lshl_add_u64 v[128:129], s[18:19], 0, v[90:91]
	v_lshl_add_u64 v[124:125], s[20:21], 0, v[96:97]
	v_lshl_add_u64 v[120:121], s[18:19], 0, v[96:97]
	s_add_i32 s12, s12, 32
	v_lshl_add_u64 v[92:93], v[92:93], 0, s[14:15]
	v_lshl_add_u64 v[94:95], v[94:95], 0, s[16:17]
	s_cmp_lt_i32 s12, s2
	s_waitcnt vmcnt(0) lgkmcnt(0)
	v_pk_add_f32 v[48:49], v[48:49], 1.0 op_sel_hi:[1,0]
	v_pk_add_f32 v[46:47], v[46:47], 1.0 op_sel_hi:[1,0]
	v_pk_fma_f32 v[48:49], v[48:49], v[76:77], v[54:55]
	v_pk_fma_f32 v[46:47], v[46:47], v[74:75], v[52:53]
	v_bfe_u32 v53, v48, 16, 1
	v_bfe_u32 v51, v46, 16, 1
	v_bfe_u32 v52, v47, 16, 1
	v_bfe_u32 v54, v49, 16, 1
	v_add3_u32 v46, v46, v51, s22
	v_add3_u32 v48, v48, v53, s22
	v_add3_u32 v47, v47, v52, s22
	v_add3_u32 v49, v49, v54, s22
	v_lshrrev_b32_e32 v46, 16, v46
	v_lshrrev_b32_e32 v48, 16, v48
	v_and_or_b32 v46, v47, s23, v46
	v_and_or_b32 v47, v49, s23, v48
	global_store_dwordx2 v[102:103], v[46:47], off offset:512
	global_load_dwordx4 v[46:49], v[146:147], off
	s_nop 0
	global_load_dwordx4 v[52:55], v[142:143], off
	s_waitcnt vmcnt(0) lgkmcnt(0)
	v_pk_add_f32 v[48:49], v[48:49], 1.0 op_sel_hi:[1,0]
	v_pk_add_f32 v[46:47], v[46:47], 1.0 op_sel_hi:[1,0]
	v_pk_fma_f32 v[48:49], v[72:73], v[48:49], v[54:55]
	v_pk_fma_f32 v[46:47], v[70:71], v[46:47], v[52:53]
	v_bfe_u32 v53, v48, 16, 1
	v_bfe_u32 v51, v46, 16, 1
	v_bfe_u32 v52, v47, 16, 1
	v_bfe_u32 v54, v49, 16, 1
	v_add3_u32 v46, v46, v51, s22
	v_add3_u32 v48, v48, v53, s22
	v_add3_u32 v47, v47, v52, s22
	v_add3_u32 v49, v49, v54, s22
	v_lshrrev_b32_e32 v46, 16, v46
	v_lshrrev_b32_e32 v48, 16, v48
	v_and_or_b32 v46, v47, s23, v46
	v_and_or_b32 v47, v49, s23, v48
	global_store_dwordx2 v[102:103], v[46:47], off offset:1024
	global_load_dwordx4 v[46:49], v[140:141], off
	s_nop 0
	global_load_dwordx4 v[52:55], v[134:135], off
	s_waitcnt vmcnt(0) lgkmcnt(0)
	v_pk_add_f32 v[48:49], v[48:49], 1.0 op_sel_hi:[1,0]
	v_pk_add_f32 v[46:47], v[46:47], 1.0 op_sel_hi:[1,0]
	v_pk_fma_f32 v[48:49], v[68:69], v[48:49], v[54:55]
	v_pk_fma_f32 v[46:47], v[66:67], v[46:47], v[52:53]
	v_bfe_u32 v53, v48, 16, 1
	v_bfe_u32 v51, v46, 16, 1
	v_bfe_u32 v52, v47, 16, 1
	v_bfe_u32 v54, v49, 16, 1
	v_add3_u32 v46, v46, v51, s22
	v_add3_u32 v48, v48, v53, s22
	v_add3_u32 v47, v47, v52, s22
	v_add3_u32 v49, v49, v54, s22
	v_lshrrev_b32_e32 v46, 16, v46
	v_lshrrev_b32_e32 v48, 16, v48
	v_and_or_b32 v46, v47, s23, v46
	v_and_or_b32 v47, v49, s23, v48
	global_store_dwordx2 v[102:103], v[46:47], off offset:1536
	global_load_dwordx4 v[46:49], v[138:139], off
	s_nop 0
	global_load_dwordx4 v[52:55], v[132:133], off
	s_waitcnt vmcnt(0) lgkmcnt(0)
	v_pk_add_f32 v[48:49], v[48:49], 1.0 op_sel_hi:[1,0]
	v_pk_add_f32 v[46:47], v[46:47], 1.0 op_sel_hi:[1,0]
	v_pk_fma_f32 v[48:49], v[48:49], v[64:65], v[54:55]
	v_pk_fma_f32 v[46:47], v[46:47], v[62:63], v[52:53]
	v_bfe_u32 v53, v48, 16, 1
	v_bfe_u32 v51, v46, 16, 1
	v_bfe_u32 v52, v47, 16, 1
	v_bfe_u32 v54, v49, 16, 1
	v_add3_u32 v46, v46, v51, s22
	v_add3_u32 v48, v48, v53, s22
	v_add3_u32 v47, v47, v52, s22
	v_add3_u32 v49, v49, v54, s22
	v_lshrrev_b32_e32 v46, 16, v46
	v_lshrrev_b32_e32 v48, 16, v48
	v_and_or_b32 v46, v47, s23, v46
	v_and_or_b32 v47, v49, s23, v48
	global_store_dwordx2 v[102:103], v[46:47], off offset:2048
	global_load_dwordx4 v[46:49], v[130:131], off
	s_nop 0
	global_load_dwordx4 v[52:55], v[126:127], off
	s_waitcnt vmcnt(0) lgkmcnt(0)
	v_pk_add_f32 v[48:49], v[48:49], 1.0 op_sel_hi:[1,0]
	v_pk_add_f32 v[46:47], v[46:47], 1.0 op_sel_hi:[1,0]
	v_pk_fma_f32 v[48:49], v[48:49], v[60:61], v[54:55]
	v_pk_fma_f32 v[46:47], v[46:47], v[58:59], v[52:53]
	v_bfe_u32 v53, v48, 16, 1
	v_bfe_u32 v51, v46, 16, 1
	v_bfe_u32 v52, v47, 16, 1
	v_bfe_u32 v54, v49, 16, 1
	v_add3_u32 v46, v46, v51, s22
	v_add3_u32 v48, v48, v53, s22
	v_add3_u32 v47, v47, v52, s22
	v_add3_u32 v49, v49, v54, s22
	v_lshrrev_b32_e32 v46, 16, v46
	v_lshrrev_b32_e32 v48, 16, v48
	v_and_or_b32 v46, v47, s23, v46
	v_and_or_b32 v47, v49, s23, v48
	global_store_dwordx2 v[102:103], v[46:47], off offset:2560
	global_load_dwordx4 v[46:49], v[122:123], off
	s_nop 0
	global_load_dwordx4 v[52:55], v[118:119], off
	v_pk_add_f32 v[58:59], v[164:165], v[164:165] op_sel:[0,1] op_sel_hi:[1,0]
	v_pk_add_f32 v[60:61], v[158:159], v[160:161]
	v_mov_b32_e32 v59, v215
	s_waitcnt vmcnt(0) lgkmcnt(0)
	v_pk_add_f32 v[48:49], v[48:49], 1.0 op_sel_hi:[1,0]
	v_pk_add_f32 v[46:47], v[46:47], 1.0 op_sel_hi:[1,0]
	v_pk_fma_f32 v[48:49], v[48:49], v[56:57], v[54:55]
	v_pk_fma_f32 v[46:47], v[46:47], v[82:83], v[52:53]
	v_bfe_u32 v53, v48, 16, 1
	v_bfe_u32 v51, v46, 16, 1
	v_bfe_u32 v52, v47, 16, 1
	v_bfe_u32 v54, v49, 16, 1
	v_add3_u32 v46, v46, v51, s22
	v_add3_u32 v48, v48, v53, s22
	v_add3_u32 v47, v47, v52, s22
	v_add3_u32 v49, v49, v54, s22
	v_lshrrev_b32_e32 v46, 16, v46
	v_lshrrev_b32_e32 v48, 16, v48
	v_and_or_b32 v46, v47, s23, v46
	v_and_or_b32 v47, v49, s23, v48
	global_store_dwordx2 v[102:103], v[46:47], off offset:3072
	global_load_dwordx4 v[46:49], v[116:117], off
	s_nop 0
	global_load_dwordx4 v[52:55], v[114:115], off
	v_pk_add_f32 v[56:57], v[162:163], v[162:163] op_sel:[0,1] op_sel_hi:[1,0]
	s_waitcnt vmcnt(0) lgkmcnt(0)
	v_pk_add_f32 v[48:49], v[48:49], 1.0 op_sel_hi:[1,0]
	v_pk_add_f32 v[46:47], v[46:47], 1.0 op_sel_hi:[1,0]
	v_pk_fma_f32 v[48:49], v[86:87], v[48:49], v[54:55]
	v_pk_fma_f32 v[46:47], v[84:85], v[46:47], v[52:53]
	v_bfe_u32 v53, v48, 16, 1
	v_bfe_u32 v51, v46, 16, 1
	v_bfe_u32 v52, v47, 16, 1
	v_bfe_u32 v54, v49, 16, 1
	v_add3_u32 v46, v46, v51, s22
	v_add3_u32 v48, v48, v53, s22
	v_add3_u32 v47, v47, v52, s22
	v_add3_u32 v49, v49, v54, s22
	v_lshrrev_b32_e32 v46, 16, v46
	v_lshrrev_b32_e32 v48, 16, v48
	v_and_or_b32 v46, v47, s23, v46
	v_and_or_b32 v47, v49, s23, v48
	global_store_dwordx2 v[102:103], v[46:47], off offset:3584
	global_load_dwordx4 v[46:49], v[156:157], off
	s_nop 0
	global_load_dwordx4 v[52:55], v[112:113], off
	v_mov_b32_e32 v57, v214
	s_waitcnt vmcnt(0) lgkmcnt(0)
	v_pk_add_f32 v[48:49], v[48:49], 1.0 op_sel_hi:[1,0]
	v_pk_add_f32 v[46:47], v[46:47], 1.0 op_sel_hi:[1,0]
	v_pk_fma_f32 v[48:49], v[48:49], v[174:175], v[54:55]
	v_pk_fma_f32 v[46:47], v[46:47], v[88:89], v[52:53]
	v_bfe_u32 v53, v48, 16, 1
	v_bfe_u32 v51, v46, 16, 1
	v_bfe_u32 v52, v47, 16, 1
	v_bfe_u32 v54, v49, 16, 1
	v_add3_u32 v46, v46, v51, s22
	v_add3_u32 v48, v48, v53, s22
	v_add3_u32 v47, v47, v52, s22
	v_add3_u32 v49, v49, v54, s22
	v_lshrrev_b32_e32 v46, 16, v46
	v_lshrrev_b32_e32 v48, 16, v48
	v_and_or_b32 v46, v47, s23, v46
	v_and_or_b32 v47, v49, s23, v48
	global_store_dwordx2 v[104:105], v[46:47], off
	global_load_dwordx4 v[46:49], v[154:155], off
	s_nop 0
	global_load_dwordx4 v[52:55], v[106:107], off
	v_pk_mul_f32 v[44:45], v[44:45], v[50:51] op_sel_hi:[1,0]
	v_pk_mul_f32 v[42:43], v[42:43], v[50:51] op_sel_hi:[1,0]
	v_pk_mul_f32 v[44:45], v[8:9], v[44:45]
	v_pk_mul_f32 v[42:43], v[6:7], v[42:43]
	s_waitcnt vmcnt(0) lgkmcnt(0)
	v_pk_add_f32 v[48:49], v[48:49], 1.0 op_sel_hi:[1,0]
	v_pk_add_f32 v[46:47], v[46:47], 1.0 op_sel_hi:[1,0]
	v_pk_fma_f32 v[44:45], v[48:49], v[44:45], v[54:55]
	v_pk_fma_f32 v[42:43], v[46:47], v[42:43], v[52:53]
	v_bfe_u32 v48, v44, 16, 1
	v_bfe_u32 v46, v42, 16, 1
	v_bfe_u32 v47, v43, 16, 1
	v_bfe_u32 v49, v45, 16, 1
	v_add3_u32 v42, v42, v46, s22
	v_add3_u32 v44, v44, v48, s22
	v_add3_u32 v43, v43, v47, s22
	v_add3_u32 v45, v45, v49, s22
	v_lshrrev_b32_e32 v42, 16, v42
	v_lshrrev_b32_e32 v44, 16, v44
	v_and_or_b32 v42, v43, s23, v42
	v_and_or_b32 v43, v45, s23, v44
	global_store_dwordx2 v[104:105], v[42:43], off offset:512
	global_load_dwordx4 v[42:45], v[150:151], off
	s_nop 0
	global_load_dwordx4 v[46:49], v[110:111], off
	v_pk_add_f32 v[52:53], v[56:57], v[58:59]
	s_waitcnt vmcnt(0) lgkmcnt(0)
	v_pk_add_f32 v[44:45], v[44:45], 1.0 op_sel_hi:[1,0]
	v_pk_add_f32 v[52:53], v[52:53], v[60:61]
	v_pk_add_f32 v[42:43], v[42:43], 1.0 op_sel_hi:[1,0]
	v_add_f32_e32 v51, v52, v53
	ds_bpermute_b32 v52, v1, v51
	s_waitcnt lgkmcnt(0)
	v_add_f32_e32 v51, v51, v52
	ds_bpermute_b32 v52, v167, v51
	s_waitcnt lgkmcnt(0)
	v_add_f32_e32 v51, v51, v52
	v_pk_mul_f32 v[40:41], v[40:41], v[50:51] op_sel_hi:[1,0]
	v_pk_mul_f32 v[38:39], v[38:39], v[50:51] op_sel_hi:[1,0]
	v_pk_mul_f32 v[40:41], v[12:13], v[40:41]
	v_pk_mul_f32 v[38:39], v[10:11], v[38:39]
	v_pk_fma_f32 v[40:41], v[44:45], v[40:41], v[48:49]
	v_pk_fma_f32 v[38:39], v[42:43], v[38:39], v[46:47]
	v_bfe_u32 v44, v40, 16, 1
	v_bfe_u32 v42, v38, 16, 1
	v_bfe_u32 v43, v39, 16, 1
	v_bfe_u32 v45, v41, 16, 1
	v_add3_u32 v38, v38, v42, s22
	v_add3_u32 v40, v40, v44, s22
	v_add3_u32 v39, v39, v43, s22
	v_add3_u32 v41, v41, v45, s22
	v_lshrrev_b32_e32 v38, 16, v38
	v_lshrrev_b32_e32 v40, 16, v40
	v_and_or_b32 v38, v39, s23, v38
	v_and_or_b32 v39, v41, s23, v40
	global_store_dwordx2 v[104:105], v[38:39], off offset:1024
	global_load_dwordx4 v[38:41], v[136:137], off
	s_nop 0
	global_load_dwordx4 v[42:45], v[108:109], off
	v_pk_mul_f32 v[36:37], v[36:37], v[50:51] op_sel_hi:[1,0]
	v_pk_mul_f32 v[34:35], v[34:35], v[50:51] op_sel_hi:[1,0]
	v_pk_mul_f32 v[36:37], v[16:17], v[36:37]
	v_pk_mul_f32 v[34:35], v[14:15], v[34:35]
	ds_bpermute_b32 v46, v168, v51
	s_waitcnt lgkmcnt(0)
	v_add_f32_e32 v46, v51, v46
	ds_bpermute_b32 v47, v169, v46
	s_waitcnt lgkmcnt(0)
	v_add_f32_e32 v46, v46, v47
	ds_bpermute_b32 v47, v170, v46
	s_waitcnt lgkmcnt(0)
	v_add_f32_e32 v46, v46, v47
	ds_bpermute_b32 v47, v171, v46
	s_waitcnt lgkmcnt(0)
	v_add_f32_e32 v46, v46, v47
	v_fmamk_f32 v46, v46, 0x3a800000, v172
	v_mul_f32_e32 v47, 0x4f800000, v46
	v_cmp_gt_f32_e32 vcc, s13, v46
	s_waitcnt vmcnt(0)
	v_pk_add_f32 v[40:41], v[40:41], 1.0 op_sel_hi:[1,0]
	v_pk_add_f32 v[38:39], v[38:39], 1.0 op_sel_hi:[1,0]
	v_pk_fma_f32 v[36:37], v[36:37], v[40:41], v[44:45]
	v_pk_fma_f32 v[34:35], v[34:35], v[38:39], v[42:43]
	v_bfe_u32 v40, v36, 16, 1
	v_bfe_u32 v38, v34, 16, 1
	v_bfe_u32 v39, v35, 16, 1
	v_bfe_u32 v41, v37, 16, 1
	v_add3_u32 v34, v34, v38, s22
	v_add3_u32 v36, v36, v40, s22
	v_add3_u32 v35, v35, v39, s22
	v_add3_u32 v37, v37, v41, s22
	v_lshrrev_b32_e32 v34, 16, v34
	v_lshrrev_b32_e32 v36, 16, v36
	v_and_or_b32 v34, v35, s23, v34
	v_and_or_b32 v35, v37, s23, v36
	global_store_dwordx2 v[104:105], v[34:35], off offset:1536
	global_load_dwordx4 v[34:37], v[144:145], off
	s_nop 0
	global_load_dwordx4 v[38:41], v[128:129], off
	v_cndmask_b32_e32 v42, v46, v47, vcc
	v_sqrt_f32_e32 v43, v42
	s_waitcnt vmcnt(0) lgkmcnt(0)
	v_pk_add_f32 v[36:37], v[36:37], 1.0 op_sel_hi:[1,0]
	v_add_u32_e32 v44, -1, v43
	v_add_u32_e32 v45, 1, v43
	v_fma_f32 v46, -v44, v43, v42
	v_fma_f32 v47, -v45, v43, v42
	v_cmp_ge_f32_e64 s[6:7], 0, v46
	v_pk_add_f32 v[34:35], v[34:35], 1.0 op_sel_hi:[1,0]
	s_nop 0
	v_cndmask_b32_e64 v43, v43, v44, s[6:7]
	v_cmp_lt_f32_e64 s[6:7], 0, v47
	s_nop 1
	v_cndmask_b32_e64 v43, v43, v45, s[6:7]
	v_mul_f32_e32 v44, 0x37800000, v43
	v_cndmask_b32_e32 v43, v43, v44, vcc
	v_cmp_class_f32_e32 vcc, v42, v173
	s_nop 1
	v_cndmask_b32_e32 v42, v43, v42, vcc
	v_div_scale_f32 v43, s[6:7], v42, v42, 1.0
	v_rcp_f32_e32 v45, v43
	v_div_scale_f32 v44, vcc, 1.0, v42, 1.0
	v_fma_f32 v46, -v43, v45, 1.0
	v_fmac_f32_e32 v45, v46, v45
	v_mul_f32_e32 v46, v44, v45
	v_fma_f32 v47, -v43, v46, v44
	v_fmac_f32_e32 v46, v47, v45
	v_fma_f32 v43, -v43, v46, v44
	v_div_fmas_f32 v43, v43, v45, v46
	v_div_fixup_f32 v42, v43, v42, 1.0
	v_pk_mul_f32 v[32:33], v[32:33], v[42:43] op_sel_hi:[1,0]
	v_pk_mul_f32 v[30:31], v[30:31], v[42:43] op_sel_hi:[1,0]
	v_pk_mul_f32 v[32:33], v[4:5], v[32:33]
	v_pk_mul_f32 v[30:31], v[2:3], v[30:31]
	v_pk_fma_f32 v[32:33], v[36:37], v[32:33], v[40:41]
	v_pk_fma_f32 v[30:31], v[34:35], v[30:31], v[38:39]
	v_bfe_u32 v36, v32, 16, 1
	v_bfe_u32 v34, v30, 16, 1
	v_bfe_u32 v35, v31, 16, 1
	v_bfe_u32 v37, v33, 16, 1
	v_add3_u32 v30, v30, v34, s22
	v_add3_u32 v32, v32, v36, s22
	v_add3_u32 v31, v31, v35, s22
	v_add3_u32 v33, v33, v37, s22
	v_lshrrev_b32_e32 v30, 16, v30
	v_lshrrev_b32_e32 v32, 16, v32
	v_and_or_b32 v30, v31, s23, v30
	v_and_or_b32 v31, v33, s23, v32
	global_store_dwordx2 v[104:105], v[30:31], off offset:2048
	global_load_dwordx4 v[30:33], v[124:125], off
	s_nop 0
	global_load_dwordx4 v[34:37], v[120:121], off
	v_pk_mul_f32 v[28:29], v[28:29], v[42:43] op_sel_hi:[1,0]
	v_pk_mul_f32 v[26:27], v[26:27], v[42:43] op_sel_hi:[1,0]
	v_pk_mul_f32 v[28:29], v[8:9], v[28:29]
	v_pk_mul_f32 v[26:27], v[6:7], v[26:27]
	v_lshl_add_u64 v[40:41], s[20:21], 0, v[98:99]
	v_lshl_add_u64 v[38:39], s[18:19], 0, v[98:99]
	v_pk_mul_f32 v[24:25], v[24:25], v[42:43] op_sel_hi:[1,0]
	v_pk_mul_f32 v[22:23], v[22:23], v[42:43] op_sel_hi:[1,0]
	v_pk_mul_f32 v[24:25], v[12:13], v[24:25]
	v_pk_mul_f32 v[22:23], v[10:11], v[22:23]
	v_pk_mul_f32 v[20:21], v[20:21], v[42:43] op_sel_hi:[1,0]
	v_pk_mul_f32 v[18:19], v[18:19], v[42:43] op_sel_hi:[1,0]
	v_pk_mul_f32 v[20:21], v[16:17], v[20:21]
	v_pk_mul_f32 v[18:19], v[14:15], v[18:19]
	s_waitcnt vmcnt(0) lgkmcnt(0)
	v_pk_add_f32 v[32:33], v[32:33], 1.0 op_sel_hi:[1,0]
	v_pk_add_f32 v[30:31], v[30:31], 1.0 op_sel_hi:[1,0]
	v_pk_fma_f32 v[28:29], v[32:33], v[28:29], v[36:37]
	v_pk_fma_f32 v[26:27], v[30:31], v[26:27], v[34:35]
	v_bfe_u32 v32, v28, 16, 1
	v_bfe_u32 v30, v26, 16, 1
	v_bfe_u32 v31, v27, 16, 1
	v_bfe_u32 v33, v29, 16, 1
	v_add3_u32 v26, v26, v30, s22
	v_add3_u32 v28, v28, v32, s22
	v_add3_u32 v27, v27, v31, s22
	v_add3_u32 v29, v29, v33, s22
	v_lshrrev_b32_e32 v26, 16, v26
	v_lshrrev_b32_e32 v28, 16, v28
	v_and_or_b32 v26, v27, s23, v26
	v_and_or_b32 v27, v29, s23, v28
	global_store_dwordx2 v[104:105], v[26:27], off offset:2560
	global_load_dwordx4 v[26:29], v[40:41], off
	s_nop 0
	global_load_dwordx4 v[30:33], v[38:39], off
	v_lshl_add_u64 v[36:37], s[20:21], 0, v[100:101]
	v_lshl_add_u64 v[34:35], s[18:19], 0, v[100:101]
	s_waitcnt vmcnt(0) lgkmcnt(0)
	v_pk_add_f32 v[28:29], v[28:29], 1.0 op_sel_hi:[1,0]
	v_pk_add_f32 v[26:27], v[26:27], 1.0 op_sel_hi:[1,0]
	v_pk_fma_f32 v[24:25], v[28:29], v[24:25], v[32:33]
	v_pk_fma_f32 v[22:23], v[26:27], v[22:23], v[30:31]
	v_bfe_u32 v28, v24, 16, 1
	v_bfe_u32 v26, v22, 16, 1
	v_bfe_u32 v27, v23, 16, 1
	v_bfe_u32 v29, v25, 16, 1
	v_add3_u32 v22, v22, v26, s22
	v_add3_u32 v24, v24, v28, s22
	v_add3_u32 v23, v23, v27, s22
	v_add3_u32 v25, v25, v29, s22
	v_lshrrev_b32_e32 v22, 16, v22
	v_lshrrev_b32_e32 v24, 16, v24
	v_and_or_b32 v22, v23, s23, v22
	v_and_or_b32 v23, v25, s23, v24
	global_store_dwordx2 v[104:105], v[22:23], off offset:3072
	global_load_dwordx4 v[22:25], v[36:37], off
	s_nop 0
	global_load_dwordx4 v[26:29], v[34:35], off
	s_waitcnt vmcnt(0) lgkmcnt(0)
	v_pk_add_f32 v[24:25], v[24:25], 1.0 op_sel_hi:[1,0]
	v_pk_add_f32 v[22:23], v[22:23], 1.0 op_sel_hi:[1,0]
	v_pk_fma_f32 v[20:21], v[20:21], v[24:25], v[28:29]
	v_pk_fma_f32 v[18:19], v[18:19], v[22:23], v[26:27]
	v_bfe_u32 v24, v20, 16, 1
	v_bfe_u32 v22, v18, 16, 1
	v_bfe_u32 v23, v19, 16, 1
	v_bfe_u32 v25, v21, 16, 1
	v_add3_u32 v18, v18, v22, s22
	v_add3_u32 v20, v20, v24, s22
	v_add3_u32 v19, v19, v23, s22
	v_add3_u32 v21, v21, v25, s22
	v_lshrrev_b32_e32 v18, 16, v18
	v_lshrrev_b32_e32 v20, 16, v20
	v_and_or_b32 v18, v19, s23, v18
	v_and_or_b32 v19, v21, s23, v20
	global_store_dwordx2 v[104:105], v[18:19], off offset:3584
	s_cbranch_scc1 .LBB0_2937

.LBB0_2957:
	s_or_b64 exec, exec, s[76:77]
	s_lshl_b32 s9, s8, 4
	s_lshl_b32 s36, s8, 6
	s_and_b32 s9, s9, 0xffffe000
	s_and_b32 s36, s36, 0x1fc0
	s_or_b32 s36, s9, s36
	s_ashr_i32 s9, s8, 31
	s_bfe_u32 s35, s8, 0x20007
	s_lshl_b64 s[44:45], s[8:9], 14
	s_lshl_b32 s37, s35, 6
	v_add_u32_e32 v2, s36, v67
	v_mov_b64_e32 v[26:27], s[12:13]
	v_lshl_add_u64 v[4:5], v[56:57], 0, s[44:45]
	v_add_u32_e32 v10, s36, v68
	v_mad_i64_i32 v[2:3], s[76:77], v2, s29, v[26:27]
	v_add_lshl_u32 v42, v55, s37, 2
	v_add_lshl_u32 v8, v66, s37, 2
	v_mov_b32_e32 v9, v43
	v_mad_i64_i32 v[10:11], s[44:45], v10, s29, v[26:27]
	v_add_co_u32_e32 v14, vcc, s30, v4
	v_lshl_add_u64 v[6:7], v[2:3], 0, v[42:43]
	v_lshl_add_u64 v[2:3], v[2:3], 0, v[8:9]
	v_lshl_add_u64 v[12:13], v[10:11], 0, v[42:43]
	v_lshl_add_u64 v[10:11], v[10:11], 0, v[8:9]
	v_addc_co_u32_e32 v15, vcc, 0, v5, vcc
	global_load_dword v34, v[4:5], off
	global_load_dword v35, v[6:7], off
	global_load_dword v36, v[2:3], off
	global_load_dword v37, v[12:13], off
	global_load_dword v38, v[10:11], off
	global_load_dword v39, v[14:15], off
	global_load_dword v40, v[14:15], off offset:2048
	global_load_dword v41, v[4:5], off offset:2048
	v_add_u32_e32 v2, s36, v69
	v_mad_i64_i32 v[2:3], s[44:45], v2, s29, v[26:27]
	v_add_u32_e32 v10, s36, v70
	v_add_u32_e32 v14, s36, v71
	v_lshl_add_u64 v[6:7], v[2:3], 0, v[42:43]
	v_mad_i64_i32 v[10:11], s[44:45], v10, s29, v[26:27]
	v_mad_i64_i32 v[14:15], s[44:45], v14, s29, v[26:27]
	v_add_co_u32_e32 v16, vcc, s4, v4
	v_lshl_add_u64 v[2:3], v[2:3], 0, v[8:9]
	v_lshl_add_u64 v[12:13], v[10:11], 0, v[42:43]
	v_lshl_add_u64 v[10:11], v[10:11], 0, v[8:9]
	v_addc_co_u32_e32 v17, vcc, 0, v5, vcc
	v_lshl_add_u64 v[18:19], v[14:15], 0, v[42:43]
	v_lshl_add_u64 v[14:15], v[14:15], 0, v[8:9]
	global_load_dword v60, v[6:7], off
	global_load_dword v61, v[2:3], off
	global_load_dword v62, v[12:13], off
	global_load_dword v63, v[10:11], off
	global_load_dword v64, v[16:17], off
	global_load_dword v65, v[18:19], off
	global_load_dword v106, v[14:15], off
	global_load_dword v107, v[16:17], off offset:2048
	v_add_u32_e32 v20, s36, v72
	v_mad_i64_i32 v[20:21], s[44:45], v20, s29, v[26:27]
	v_add_u32_e32 v10, s36, v73
	v_add_u32_e32 v14, s36, v74
	v_lshl_add_u64 v[2:3], v[20:21], 0, v[42:43]
	v_mad_i64_i32 v[10:11], s[44:45], v10, s29, v[26:27]
	v_add_co_u32_e32 v4, vcc, s29, v4
	v_mad_i64_i32 v[14:15], s[44:45], v14, s29, v[26:27]
	v_lshl_add_u64 v[6:7], v[20:21], 0, v[8:9]
	v_addc_co_u32_e32 v5, vcc, 0, v5, vcc
	v_lshl_add_u64 v[12:13], v[10:11], 0, v[42:43]
	v_lshl_add_u64 v[10:11], v[10:11], 0, v[8:9]
	v_lshl_add_u64 v[16:17], v[14:15], 0, v[42:43]
	v_lshl_add_u64 v[8:9], v[14:15], 0, v[8:9]
	global_load_dword v42, v[2:3], off
	global_load_dword v108, v[6:7], off
	global_load_dword v109, v[4:5], off
	global_load_dword v110, v[12:13], off
	global_load_dword v111, v[10:11], off
	global_load_dword v112, v[16:17], off
	global_load_dword v113, v[8:9], off
	global_load_dword v114, v[4:5], off offset:2048
	s_lshl_b64 s[8:9], s[8:9], 15
	v_add_u32_e32 v2, s36, v75
	v_lshl_add_u64 v[28:29], v[44:45], 0, s[8:9]
	v_mad_i64_i32 v[2:3], s[8:9], v2, s29, v[26:27]
	s_lshl_b32 s70, s35, 9
	v_lshl_add_u64 v[2:3], v[2:3], 0, s[70:71]
	v_mov_b32_e32 v59, v43
	v_add_u32_e32 v10, s36, v76
	v_lshl_add_u64 v[2:3], v[2:3], 0, v[58:59]
	v_mad_i64_i32 v[10:11], s[8:9], v10, s29, v[26:27]
	v_add_co_u32_e32 v2, vcc, s30, v2
	v_lshl_add_u64 v[10:11], v[10:11], 0, s[70:71]
	v_add_u32_e32 v18, s36, v77
	v_addc_co_u32_e32 v3, vcc, 0, v3, vcc
	v_lshl_add_u64 v[10:11], v[10:11], 0, v[58:59]
	v_mad_i64_i32 v[18:19], s[8:9], v18, s29, v[26:27]
	v_add_co_u32_e32 v10, vcc, s30, v10
	v_lshl_add_u64 v[18:19], v[18:19], 0, s[70:71]
	v_add_u32_e32 v30, s36, v78
	v_addc_co_u32_e32 v11, vcc, 0, v11, vcc
	v_lshl_add_u64 v[18:19], v[18:19], 0, v[58:59]
	v_mad_i64_i32 v[26:27], s[8:9], v30, s29, v[26:27]
	v_add_co_u32_e32 v18, vcc, s30, v18
	v_lshl_add_u64 v[26:27], v[26:27], 0, s[70:71]
	s_nop 0
	v_addc_co_u32_e32 v19, vcc, 0, v19, vcc
	v_lshl_add_u64 v[26:27], v[26:27], 0, v[58:59]
	v_add_co_u32_e32 v26, vcc, s30, v26
	v_lshl_add_u64 v[6:7], v[46:47], 2, v[28:29]
	v_lshl_add_u64 v[14:15], v[48:49], 2, v[28:29]
	v_lshl_add_u64 v[22:23], v[50:51], 2, v[28:29]
	v_addc_co_u32_e32 v27, vcc, 0, v27, vcc
	v_lshl_add_u64 v[30:31], v[52:53], 2, v[28:29]
	global_load_dwordx4 v[2:5], v[2:3], off offset:3168
	s_nop 0
	global_load_dwordx4 v[6:9], v[6:7], off
	s_nop 0
	global_load_dwordx4 v[10:13], v[10:11], off offset:3168
	s_nop 0
	global_load_dwordx4 v[14:17], v[14:15], off
	s_nop 0
	global_load_dwordx4 v[18:21], v[18:19], off offset:3168
	s_nop 0
	global_load_dwordx4 v[22:25], v[22:23], off
	s_nop 0
	global_load_dwordx4 v[26:29], v[26:27], off offset:3168
	s_nop 0
	global_load_dwordx4 v[30:33], v[30:31], off
	s_waitcnt vmcnt(0) lgkmcnt(0)
	v_mul_f32_e32 v59, 0x3fb8aa3b, v34
	v_mul_f32_e32 v34, 0xbfb8aa3b, v34
	v_exp_f32_e32 v34, v34
	v_exp_f32_e32 v59, v59
	v_mul_f32_e32 v35, 0x3e000000, v35
	v_mul_f32_e32 v34, v36, v34
	v_mul_f32_e32 v36, 0x3fb8aa3b, v41
	v_exp_f32_e32 v36, v36
	v_mul_f32_e32 v35, v35, v59
	v_mul_f32_e32 v41, 0xbfb8aa3b, v41
	s_barrier
	v_exp_f32_e32 v41, v41
	ds_write2st64_b32 v79, v35, v34 offset0:65 offset1:130
	v_mul_f32_e32 v34, 0x3e000000, v37
	v_mul_f32_e32 v34, v34, v36
	v_mul_f32_e32 v36, 0x3fb8aa3b, v39
	v_mul_f32_e32 v37, 0xbfb8aa3b, v39
	v_exp_f32_e32 v36, v36
	v_exp_f32_e32 v37, v37
	v_mul_f32_e32 v35, v38, v41
	ds_write2st64_b32 v80, v34, v35 offset0:65 offset1:130
	v_mul_f32_e32 v34, 0x3e000000, v60
	v_mul_f32_e32 v34, v34, v36
	v_mul_f32_e32 v35, v61, v37
	v_mul_f32_e32 v36, 0x3fb8aa3b, v40
	v_mul_f32_e32 v37, 0xbfb8aa3b, v40
	v_exp_f32_e32 v36, v36
	v_exp_f32_e32 v37, v37
	ds_write2st64_b32 v81, v34, v35 offset0:65 offset1:130
	v_mul_f32_e32 v34, 0x3e000000, v62
	v_mul_f32_e32 v34, v34, v36
	v_mul_f32_e32 v35, v63, v37
	v_mul_f32_e32 v36, 0x3fb8aa3b, v64
	v_mul_f32_e32 v37, 0xbfb8aa3b, v64
	v_exp_f32_e32 v36, v36
	v_exp_f32_e32 v37, v37
	ds_write2st64_b32 v82, v34, v35 offset0:65 offset1:130
	v_mul_f32_e32 v34, 0x3e000000, v65
	v_mul_f32_e32 v34, v34, v36
	v_mul_f32_e32 v35, v106, v37
	v_mul_f32_e32 v36, 0x3fb8aa3b, v107
	v_mul_f32_e32 v37, 0xbfb8aa3b, v107
	v_exp_f32_e32 v36, v36
	v_exp_f32_e32 v37, v37
	ds_write2st64_b32 v83, v34, v35 offset0:65 offset1:130
	v_mul_f32_e32 v34, 0x3e000000, v42
	v_mul_f32_e32 v34, v34, v36
	v_mul_f32_e32 v35, v108, v37
	v_mul_f32_e32 v36, 0x3fb8aa3b, v109
	v_mul_f32_e32 v37, 0xbfb8aa3b, v109
	v_exp_f32_e32 v36, v36
	v_exp_f32_e32 v37, v37
	ds_write2st64_b32 v84, v34, v35 offset0:65 offset1:130
	v_mul_f32_e32 v34, 0x3e000000, v110
	v_mul_f32_e32 v34, v34, v36
	v_mul_f32_e32 v35, v111, v37
	v_mul_f32_e32 v36, 0x3fb8aa3b, v114
	v_mul_f32_e32 v37, 0xbfb8aa3b, v114
	v_exp_f32_e32 v36, v36
	v_exp_f32_e32 v37, v37
	ds_write2st64_b32 v85, v34, v35 offset0:65 offset1:130
	v_mul_f32_e32 v34, 0x3e000000, v112
	v_mul_f32_e32 v34, v34, v36
	v_mul_f32_e32 v35, v113, v37
	ds_write2st64_b32 v86, v34, v35 offset0:65 offset1:130
	ds_write_b128 v87, v[2:5] offset:49920
	ds_write_b128 v88, v[6:9]
	ds_write_b128 v87, v[10:13] offset:58112
	ds_write_b128 v89, v[14:17]
	ds_write_b128 v90, v[18:21]
	ds_write_b128 v91, v[22:25]
	ds_write_b128 v92, v[26:29]
	ds_write_b128 v93, v[30:33]
	v_mov_b32_e32 v2, 0
	s_lshl_b32 s35, s35, 7
	s_mov_b32 s8, 32
	v_mov_b32_e32 v18, v97
	v_mov_b32_e32 v19, v96
	v_mov_b32_e32 v3, v2
	v_mov_b32_e32 v4, v2
	v_mov_b32_e32 v5, v2
	v_mov_b32_e32 v6, v2
	v_mov_b32_e32 v7, v2
	v_mov_b32_e32 v8, v2
	v_mov_b32_e32 v9, v2
	v_mov_b32_e32 v10, v2
	v_mov_b32_e32 v11, v2
	v_mov_b32_e32 v12, v2
	v_mov_b32_e32 v13, v2
	v_mov_b32_e32 v14, v2
	v_mov_b32_e32 v15, v2
	v_mov_b32_e32 v16, v2
	v_mov_b32_e32 v17, v2
	s_waitcnt lgkmcnt(0)
	s_barrier

.LBB0_2965:
	ds_read2_b32 v[20:21], v18 offset1:2
	ds_read2st64_b32 v[22:23], v19 offset1:4
	s_add_i32 s8, s8, -8
	s_cmp_eq_u32 s8, 0
	s_waitcnt lgkmcnt(0)
	v_mfma_f32_32x32x2_f32 v[2:17], v20, v22, v[2:17]
	v_mfma_f32_32x32x2_f32 v[2:17], v21, v23, v[2:17]
	ds_read2_b32 v[20:21], v18 offset0:4 offset1:6
	ds_read2st64_b32 v[22:23], v19 offset0:8 offset1:12
	s_waitcnt lgkmcnt(0)
	v_mfma_f32_32x32x2_f32 v[2:17], v20, v22, v[2:17]
	v_mfma_f32_32x32x2_f32 v[2:17], v21, v23, v[2:17]
	ds_read2_b32 v[20:21], v18 offset0:8 offset1:10
	ds_read2st64_b32 v[22:23], v19 offset0:16 offset1:20
	s_waitcnt lgkmcnt(0)
	v_mfma_f32_32x32x2_f32 v[2:17], v20, v22, v[2:17]
	v_mfma_f32_32x32x2_f32 v[2:17], v21, v23, v[2:17]
	ds_read2_b32 v[20:21], v18 offset0:12 offset1:14
	ds_read2st64_b32 v[22:23], v19 offset0:24 offset1:28
	v_add_u32_e32 v19, 0x2000, v19
	v_add_u32_e32 v18, 64, v18
	s_waitcnt lgkmcnt(0)
	v_mfma_f32_32x32x2_f32 v[2:17], v20, v22, v[2:17]
	v_mfma_f32_32x32x2_f32 v[2:17], v21, v23, v[2:17]
	s_cbranch_scc0 .LBB0_2965
	v_add_u32_e32 v18, 0xc200, v103
	s_barrier
	s_nop 14
	ds_write2_b32 v18, v2, v3 offset0:64 offset1:196
	v_add_u32_e32 v2, 0xc600, v103
	ds_write2_b32 v2, v4, v5 offset0:72 offset1:204
	v_add_u32_e32 v2, 0xd200, v103
	ds_write2_b32 v2, v6, v7 offset0:96 offset1:228
	v_add_u32_e32 v2, 0xd600, v103
	ds_write2_b32 v2, v8, v9 offset0:104 offset1:236
	v_add_u32_e32 v2, 0xe400, v103
	ds_write2_b32 v2, v10, v11 offset1:132
	v_add_u32_e32 v2, 0xe800, v103
	ds_write2_b32 v2, v12, v13 offset0:8 offset1:140
	v_add_u32_e32 v2, 0xf400, v103
	ds_write2_b32 v2, v14, v15 offset0:32 offset1:164
	v_add_u32_e32 v2, 0xf800, v103
	v_mov_b64_e32 v[18:19], s[0:1]
	ds_write2_b32 v2, v16, v17 offset0:40 offset1:172
	s_waitcnt lgkmcnt(0)
	s_barrier
	ds_read_b128 v[14:17], v95 offset:49920
	ds_read_b128 v[10:13], v95 offset:49936
	ds_read_b128 v[6:9], v95 offset:49952
	ds_read_b128 v[2:5], v95 offset:49968
	global_load_dwordx2 v[22:23], v[18:19], off offset:168 sc0 sc1
	s_waitcnt vmcnt(0)
	v_add_u32_e32 v60, s36, v94
	v_mov_b64_e32 v[18:19], s[12:13]
	v_and_b32_e32 v21, 64, v166
	s_lshl_b32 s70, s35, 2
	v_mad_i64_i32 v[18:19], s[8:9], v60, s29, v[18:19]
	v_xor_b32_e32 v20, 1, v166
	v_lshlrev_b32_e32 v42, 2, v54
	v_add_u32_e32 v59, 64, v21
	v_lshl_add_u64 v[18:19], v[18:19], 0, s[70:71]
	v_cmp_lt_i32_e32 vcc, v20, v59
	v_lshl_add_u64 v[30:31], v[18:19], 0, v[42:43]
	s_waitcnt lgkmcnt(0)
	v_mov_b32_e32 v26, v15
	v_cndmask_b32_e32 v20, v166, v20, vcc
	v_add_co_u32_e32 v18, vcc, s4, v30
	v_lshlrev_b32_e32 v61, 2, v20
	s_nop 0
	v_addc_co_u32_e32 v19, vcc, 0, v31, vcc
	global_load_dwordx4 v[18:21], v[18:19], off offset:1184
	v_mov_b32_e32 v27, v11
	v_mov_b32_e32 v24, v14
	v_mov_b32_e32 v25, v10
	v_mov_b32_e32 v36, v7
	v_mov_b32_e32 v37, v3
	v_pk_mul_f32 v[26:27], v[26:27], v[26:27]
	v_mov_b32_e32 v28, v16
	v_mov_b32_e32 v29, v12
	v_mov_b32_e32 v34, v6
	v_mov_b32_e32 v35, v2
	v_pk_mul_f32 v[36:37], v[36:37], v[36:37]
	v_pk_fma_f32 v[24:25], v[24:25], v[24:25], v[26:27]
	v_mov_b32_e32 v32, v17
	v_mov_b32_e32 v33, v13
	v_mov_b32_e32 v38, v8
	v_mov_b32_e32 v39, v4
	v_pk_fma_f32 v[26:27], v[34:35], v[34:35], v[36:37]
	v_pk_fma_f32 v[24:25], v[28:29], v[28:29], v[24:25]
	v_mov_b32_e32 v40, v9
	v_mov_b32_e32 v41, v5
	v_pk_fma_f32 v[26:27], v[38:39], v[38:39], v[26:27]
	v_pk_fma_f32 v[24:25], v[32:33], v[32:33], v[24:25]
	v_pk_fma_f32 v[26:27], v[40:41], v[40:41], v[26:27]
	v_add_f32_e32 v24, v24, v25
	v_add_f32_e32 v24, v24, v26
	v_add_f32_e32 v24, v24, v27
	ds_bpermute_b32 v25, v61, v24
	v_xor_b32_e32 v26, 2, v166
	v_cmp_lt_i32_e32 vcc, v26, v59
	v_lshl_add_u64 v[62:63], v[30:31], 0, s[72:73]
	v_mov_b32_e32 v38, v14
	v_cndmask_b32_e32 v26, v166, v26, vcc
	v_lshlrev_b32_e32 v26, 2, v26
	s_waitcnt lgkmcnt(0)
	v_add_f32_e32 v24, v24, v25
	ds_bpermute_b32 v25, v26, v24
	v_ashrrev_i32_e32 v61, 31, v60
	s_lshl_b32 s70, s35, 1
	s_mov_b64 s[76:77], 0
	s_waitcnt lgkmcnt(0)
	v_add_f32_e32 v32, v24, v25
	v_lshl_add_u64 v[64:65], v[22:23], 0, v[42:43]
	global_load_dwordx4 v[26:29], v[64:65], off
	v_xor_b32_e32 v22, 4, v166
	v_cmp_lt_i32_e32 vcc, v22, v59
	s_nop 1
	v_cndmask_b32_e32 v22, v166, v22, vcc
	v_lshlrev_b32_e32 v22, 2, v22
	ds_bpermute_b32 v33, v22, v32
	global_load_dwordx4 v[22:25], v[64:65], off offset:16
	s_waitcnt lgkmcnt(0)
	v_add_f32_e32 v30, v32, v33
	v_fmamk_f32 v30, v30, 0x3c000000, v104
	v_mul_f32_e32 v31, 0x4f800000, v30
	v_cmp_gt_f32_e32 vcc, s31, v30
	s_nop 1
	v_cndmask_b32_e32 v39, v30, v31, vcc
	v_sqrt_f32_e32 v40, v39
	global_load_dwordx4 v[30:33], v[62:63], off offset:16
	global_load_dwordx4 v[34:37], v[62:63], off offset:48
	v_add_u32_e32 v14, -1, v40
	v_add_u32_e32 v41, 1, v40
	v_fma_f32 v42, -v14, v40, v39
	v_fma_f32 v59, -v41, v40, v39
	v_cmp_ge_f32_e64 s[8:9], 0, v42
	s_nop 1
	v_cndmask_b32_e64 v14, v40, v14, s[8:9]
	v_cmp_lt_f32_e64 s[8:9], 0, v59
	s_nop 1
	v_cndmask_b32_e64 v14, v14, v41, s[8:9]
	v_mul_f32_e32 v40, 0x37800000, v14
	v_cndmask_b32_e32 v14, v14, v40, vcc
	v_cmp_class_f32_e32 vcc, v39, v105
	s_nop 1
	v_cndmask_b32_e32 v14, v14, v39, vcc
	v_div_scale_f32 v40, s[8:9], v14, v14, 1.0
	v_rcp_f32_e32 v41, v40
	v_mov_b32_e32 v39, v16
	v_div_scale_f32 v16, vcc, 1.0, v14, 1.0
	v_fma_f32 v42, -v40, v41, 1.0
	v_fmac_f32_e32 v41, v42, v41
	v_mul_f32_e32 v42, v16, v41
	v_fma_f32 v59, -v40, v42, v16
	v_fmac_f32_e32 v42, v59, v41
	v_fma_f32 v16, -v40, v42, v16
	v_div_fmas_f32 v16, v16, v41, v42
	v_div_fixup_f32 v14, v16, v14, 1.0
	v_pk_mul_f32 v[110:111], v[38:39], v[14:15] op_sel_hi:[1,0]
	s_waitcnt vmcnt(0)
	v_mul_f32_e32 v16, 0xbfb8aa3b, v18
	v_mul_f32_e32 v38, 0xbfb8aa3b, v20
	v_exp_f32_e32 v112, v16
	v_exp_f32_e32 v113, v38
	v_mul_f32_e32 v16, 0xbfb8aa3b, v19
	global_load_dwordx4 v[38:41], v[64:65], off offset:48
	global_load_dwordx4 v[106:109], v[64:65], off offset:32
	v_exp_f32_e32 v64, v16
	v_pk_add_f32 v[112:113], v[112:113], 1.0 op_sel_hi:[1,0]
	s_nop 0
	v_div_scale_f32 v16, s[8:9], v113, v113, v20
	v_rcp_f32_e32 v65, v16
	v_div_scale_f32 v59, s[8:9], v112, v112, v18
	v_rcp_f32_e32 v116, v59
	v_fma_f32 v114, -v16, v65, 1.0
	v_div_scale_f32 v42, vcc, v20, v113, v20
	v_fmac_f32_e32 v65, v114, v65
	v_fma_f32 v115, -v59, v116, 1.0
	v_mul_f32_e32 v114, v42, v65
	v_fmac_f32_e32 v116, v115, v116
	v_fma_f32 v115, -v16, v114, v42
	v_fmac_f32_e32 v114, v115, v65
	v_fma_f32 v16, -v16, v114, v42
	v_div_fmas_f32 v16, v16, v65, v114
	v_div_scale_f32 v117, s[8:9], v18, v112, v18
	v_div_fixup_f32 v113, v16, v113, v20
	v_mul_f32_e32 v20, 0xbfb8aa3b, v21
	v_mul_f32_e32 v118, v117, v116
	v_exp_f32_e32 v65, v20
	v_fma_f32 v119, -v59, v118, v117
	v_fmac_f32_e32 v118, v119, v116
	v_fma_f32 v16, -v59, v118, v117
	s_mov_b64 vcc, s[8:9]
	v_div_fmas_f32 v16, v16, v116, v118
	v_pk_add_f32 v[64:65], v[64:65], 1.0 op_sel_hi:[1,0]
	v_div_fixup_f32 v112, v16, v112, v18
	v_mov_b32_e32 v16, v15
	v_div_scale_f32 v15, s[8:9], v65, v65, v21
	v_rcp_f32_e32 v18, v15
	v_mov_b32_e32 v114, v26
	v_mov_b32_e32 v115, v28
	v_mov_b32_e32 v28, v27
	v_fma_f32 v20, -v15, v18, 1.0
	v_fmac_f32_e32 v18, v20, v18
	v_div_scale_f32 v20, vcc, v21, v65, v21
	v_mul_f32_e32 v26, v20, v18
	v_fma_f32 v27, -v15, v26, v20
	v_fmac_f32_e32 v26, v27, v18
	v_pk_mul_f32 v[16:17], v[16:17], v[14:15] op_sel_hi:[1,0]
	v_fma_f32 v15, -v15, v26, v20
	v_div_scale_f32 v20, s[8:9], v64, v64, v19
	v_rcp_f32_e32 v27, v20
	v_div_fmas_f32 v15, v15, v18, v26
	v_div_fixup_f32 v21, v15, v65, v21
	v_pk_mul_f32 v[16:17], v[28:29], v[16:17]
	v_fma_f32 v15, -v20, v27, 1.0
	v_fmac_f32_e32 v27, v15, v27
	v_div_scale_f32 v15, vcc, v19, v64, v19
	v_mul_f32_e32 v18, v15, v27
	v_fma_f32 v26, -v20, v18, v15
	v_fmac_f32_e32 v18, v26, v27
	v_fma_f32 v15, -v20, v18, v15
	v_div_fmas_f32 v15, v15, v27, v18
	v_div_fixup_f32 v20, v15, v64, v19
	v_pk_mul_f32 v[20:21], v[20:21], v[16:17]
	global_load_dwordx4 v[16:19], v[62:63], off offset:32
	s_waitcnt lgkmcnt(0)
	v_mul_f32_e32 v15, 0xbfb8aa3b, v30
	v_exp_f32_e32 v26, v15
	v_mul_f32_e32 v15, 0xbfb8aa3b, v31
	v_exp_f32_e32 v28, v15
	v_mul_f32_e32 v15, 0xbfb8aa3b, v32
	v_exp_f32_e32 v27, v15
	v_mov_b32_e32 v62, v10
	v_mov_b32_e32 v63, v12
	v_pk_mul_f32 v[62:63], v[62:63], v[14:15] op_sel_hi:[1,0]
	v_pk_add_f32 v[26:27], v[26:27], 1.0 op_sel_hi:[1,0]
	v_mov_b32_e32 v64, v22
	v_div_scale_f32 v10, s[8:9], v27, v27, v32
	v_rcp_f32_e32 v12, v10
	v_mov_b32_e32 v65, v24
	v_pk_mul_f32 v[110:111], v[114:115], v[110:111]
	v_pk_mul_f32 v[62:63], v[62:63], v[64:65]
	v_fma_f32 v15, -v10, v12, 1.0
	v_fmac_f32_e32 v12, v15, v12
	v_div_scale_f32 v15, vcc, v32, v27, v32
	v_mul_f32_e32 v22, v15, v12
	v_fma_f32 v24, -v10, v22, v15
	v_fmac_f32_e32 v22, v24, v12
	v_fma_f32 v10, -v10, v22, v15
	v_div_scale_f32 v15, s[8:9], v26, v26, v30
	v_rcp_f32_e32 v24, v15
	v_div_fmas_f32 v10, v10, v12, v22
	v_div_fixup_f32 v27, v10, v27, v32
	v_pk_mul_f32 v[110:111], v[112:113], v[110:111]
	v_fma_f32 v10, -v15, v24, 1.0
	v_fmac_f32_e32 v24, v10, v24
	v_div_scale_f32 v10, vcc, v30, v26, v30
	v_mul_f32_e32 v12, v10, v24
	v_fma_f32 v22, -v15, v12, v10
	v_fmac_f32_e32 v12, v22, v24
	v_fma_f32 v10, -v15, v12, v10
	v_div_fmas_f32 v10, v10, v24, v12
	v_mul_f32_e32 v12, 0xbfb8aa3b, v33
	v_exp_f32_e32 v29, v12
	v_div_fixup_f32 v26, v10, v26, v30
	v_mov_b32_e32 v12, v11
	v_mov_b32_e32 v24, v23
	v_pk_add_f32 v[10:11], v[28:29], 1.0 op_sel_hi:[1,0]
	v_pk_mul_f32 v[26:27], v[62:63], v[26:27]
	v_div_scale_f32 v15, s[8:9], v11, v11, v33
	v_rcp_f32_e32 v22, v15
	v_pk_mul_f32 v[12:13], v[12:13], v[14:15] op_sel_hi:[1,0]
	v_lshlrev_b32_e32 v42, 1, v54
	v_pk_mul_f32 v[12:13], v[12:13], v[24:25]
	v_fma_f32 v23, -v15, v22, 1.0
	v_fmac_f32_e32 v22, v23, v22
	v_div_scale_f32 v23, vcc, v33, v11, v33
	v_mul_f32_e32 v24, v23, v22
	v_fma_f32 v25, -v15, v24, v23
	v_fmac_f32_e32 v24, v25, v22
	v_fma_f32 v15, -v15, v24, v23
	v_div_scale_f32 v23, s[8:9], v10, v10, v31
	v_rcp_f32_e32 v25, v23
	v_div_fmas_f32 v15, v15, v22, v24
	v_div_fixup_f32 v11, v15, v11, v33
	v_fma_f32 v15, -v23, v25, 1.0
	v_fmac_f32_e32 v25, v15, v25
	v_div_scale_f32 v15, vcc, v31, v10, v31
	v_mul_f32_e32 v22, v15, v25
	v_fma_f32 v24, -v23, v22, v15
	v_fmac_f32_e32 v22, v24, v25
	v_fma_f32 v15, -v23, v22, v15
	v_div_fmas_f32 v15, v15, v25, v22
	v_div_fixup_f32 v10, v15, v10, v31
	v_pk_mul_f32 v[10:11], v[12:13], v[10:11]
	v_bfe_u32 v22, v20, 16, 1
	v_bfe_u32 v13, v10, 16, 1
	v_bfe_u32 v12, v11, 16, 1
	v_bfe_u32 v15, v21, 16, 1
	v_add3_u32 v20, v20, v22, s33
	v_add3_u32 v10, v10, v13, s33
	v_bfe_u32 v13, v111, 16, 1
	v_bfe_u32 v22, v27, 16, 1
	v_add3_u32 v15, v21, v15, s33
	v_add3_u32 v11, v11, v12, s33
	v_bfe_u32 v12, v110, 16, 1
	v_bfe_u32 v21, v26, 16, 1
	v_add3_u32 v22, v27, v22, s33
	v_add3_u32 v13, v111, v13, s33
	v_add3_u32 v21, v26, v21, s33
	v_add3_u32 v12, v110, v12, s33
	v_lshrrev_b32_e32 v24, 16, v13
	v_lshrrev_b32_e32 v13, 16, v22
	v_lshrrev_b32_e32 v23, 16, v12
	v_lshrrev_b32_e32 v12, 16, v21
	v_and_or_b32 v13, v11, s34, v13
	v_and_or_b32 v11, v15, s34, v24
	s_waitcnt vmcnt(0)
	v_mul_f32_e32 v15, 0xbfb8aa3b, v16
	v_and_or_b32 v12, v10, s34, v12
	v_and_or_b32 v10, v20, s34, v23
	v_exp_f32_e32 v20, v15
	v_mul_f32_e32 v15, 0xbfb8aa3b, v17
	v_exp_f32_e32 v22, v15
	v_mul_f32_e32 v15, 0xbfb8aa3b, v18
	v_exp_f32_e32 v21, v15
	v_mov_b32_e32 v24, v6
	v_mov_b32_e32 v25, v8
	v_pk_mul_f32 v[24:25], v[24:25], v[14:15] op_sel_hi:[1,0]
	v_pk_add_f32 v[20:21], v[20:21], 1.0 op_sel_hi:[1,0]
	v_mov_b32_e32 v26, v106
	v_div_scale_f32 v6, s[8:9], v21, v21, v18
	v_rcp_f32_e32 v8, v6
	v_mov_b32_e32 v27, v108
	v_pk_mul_f32 v[24:25], v[24:25], v[26:27]
	v_mov_b32_e32 v108, v107
	v_fma_f32 v15, -v6, v8, 1.0
	v_fmac_f32_e32 v8, v15, v8
	v_div_scale_f32 v15, vcc, v18, v21, v18
	v_mul_f32_e32 v23, v15, v8
	v_fma_f32 v26, -v6, v23, v15
	v_fmac_f32_e32 v23, v26, v8
	v_fma_f32 v6, -v6, v23, v15
	v_div_scale_f32 v15, s[8:9], v20, v20, v16
	v_rcp_f32_e32 v26, v15
	v_div_fmas_f32 v6, v6, v8, v23
	v_div_fixup_f32 v21, v6, v21, v18
	v_fma_f32 v6, -v15, v26, 1.0
	v_fmac_f32_e32 v26, v6, v26
	v_div_scale_f32 v6, vcc, v16, v20, v16
	v_mul_f32_e32 v8, v6, v26
	v_fma_f32 v18, -v15, v8, v6
	v_fmac_f32_e32 v8, v18, v26
	v_fma_f32 v6, -v15, v8, v6
	v_div_fmas_f32 v6, v6, v26, v8
	v_mul_f32_e32 v8, 0xbfb8aa3b, v19
	v_exp_f32_e32 v23, v8
	v_div_fixup_f32 v20, v6, v20, v16
	v_mov_b32_e32 v8, v7
	v_pk_mul_f32 v[20:21], v[24:25], v[20:21]
	v_pk_add_f32 v[6:7], v[22:23], 1.0 op_sel_hi:[1,0]
	s_nop 0
	v_div_scale_f32 v15, s[8:9], v7, v7, v19
	v_rcp_f32_e32 v16, v15
	v_pk_mul_f32 v[8:9], v[8:9], v[14:15] op_sel_hi:[1,0]
	v_fma_f32 v18, -v15, v16, 1.0
	v_fmac_f32_e32 v16, v18, v16
	v_div_scale_f32 v18, vcc, v19, v7, v19
	v_mul_f32_e32 v22, v18, v16
	v_fma_f32 v23, -v15, v22, v18
	v_fmac_f32_e32 v22, v23, v16
	v_fma_f32 v15, -v15, v22, v18
	v_div_scale_f32 v18, s[8:9], v6, v6, v17
	v_rcp_f32_e32 v23, v18
	v_div_fmas_f32 v15, v15, v16, v22
	v_div_fixup_f32 v7, v15, v7, v19
	v_pk_mul_f32 v[8:9], v[8:9], v[108:109]
	v_fma_f32 v15, -v18, v23, 1.0
	v_fmac_f32_e32 v23, v15, v23
	v_div_scale_f32 v15, vcc, v17, v6, v17
	v_mul_f32_e32 v16, v15, v23
	v_fma_f32 v19, -v18, v16, v15
	v_fmac_f32_e32 v16, v19, v23
	v_fma_f32 v15, -v18, v16, v15
	v_div_fmas_f32 v15, v15, v23, v16
	v_div_fixup_f32 v6, v15, v6, v17
	v_pk_mul_f32 v[6:7], v[8:9], v[6:7]
	v_mul_f32_e32 v9, 0xbfb8aa3b, v35
	v_mul_f32_e32 v8, 0xbfb8aa3b, v34
	v_exp_f32_e32 v16, v9
	v_mul_f32_e32 v9, 0xbfb8aa3b, v36
	v_exp_f32_e32 v8, v8
	v_exp_f32_e32 v9, v9
	v_mov_b32_e32 v18, v2
	v_mov_b32_e32 v19, v4
	v_pk_mul_f32 v[18:19], v[18:19], v[14:15] op_sel_hi:[1,0]
	v_pk_add_f32 v[8:9], v[8:9], 1.0 op_sel_hi:[1,0]
	v_mov_b32_e32 v22, v38
	v_div_scale_f32 v2, s[8:9], v9, v9, v36
	v_rcp_f32_e32 v4, v2
	v_mov_b32_e32 v23, v40
	v_pk_mul_f32 v[18:19], v[18:19], v[22:23]
	v_mov_b32_e32 v40, v39
	v_fma_f32 v15, -v2, v4, 1.0
	v_fmac_f32_e32 v4, v15, v4
	v_div_scale_f32 v15, vcc, v36, v9, v36
	v_mul_f32_e32 v17, v15, v4
	v_fma_f32 v22, -v2, v17, v15
	v_fmac_f32_e32 v17, v22, v4
	v_fma_f32 v2, -v2, v17, v15
	v_div_scale_f32 v15, s[8:9], v8, v8, v34
	v_rcp_f32_e32 v22, v15
	v_div_fmas_f32 v2, v2, v4, v17
	v_div_fixup_f32 v9, v2, v9, v36
	v_fma_f32 v2, -v15, v22, 1.0
	v_fmac_f32_e32 v22, v2, v22
	v_div_scale_f32 v2, vcc, v34, v8, v34
	v_mul_f32_e32 v4, v2, v22
	v_fma_f32 v17, -v15, v4, v2
	v_fmac_f32_e32 v4, v17, v22
	v_fma_f32 v2, -v15, v4, v2
	v_div_fmas_f32 v2, v2, v22, v4
	v_mul_f32_e32 v4, 0xbfb8aa3b, v37
	v_exp_f32_e32 v17, v4
	v_div_fixup_f32 v8, v2, v8, v34
	v_mov_b32_e32 v4, v3
	v_pk_mul_f32 v[8:9], v[18:19], v[8:9]
	v_pk_add_f32 v[2:3], v[16:17], 1.0 op_sel_hi:[1,0]
	s_nop 0
	v_div_scale_f32 v15, s[8:9], v3, v3, v37
	v_rcp_f32_e32 v16, v15
	v_pk_mul_f32 v[4:5], v[4:5], v[14:15] op_sel_hi:[1,0]
	v_fma_f32 v14, -v15, v16, 1.0
	v_fmac_f32_e32 v16, v14, v16
	v_div_scale_f32 v14, vcc, v37, v3, v37
	v_mul_f32_e32 v17, v14, v16
	v_fma_f32 v18, -v15, v17, v14
	v_fmac_f32_e32 v17, v18, v16
	v_fma_f32 v14, -v15, v17, v14
	v_div_scale_f32 v15, s[8:9], v2, v2, v35
	v_rcp_f32_e32 v18, v15
	v_div_fmas_f32 v14, v14, v16, v17
	v_div_fixup_f32 v3, v14, v3, v37
	v_pk_mul_f32 v[4:5], v[4:5], v[40:41]
	v_fma_f32 v14, -v15, v18, 1.0
	v_fmac_f32_e32 v18, v14, v18
	v_div_scale_f32 v14, vcc, v35, v2, v35
	v_mul_f32_e32 v16, v14, v18
	v_fma_f32 v17, -v15, v16, v14
	v_fmac_f32_e32 v16, v17, v18
	v_fma_f32 v14, -v15, v16, v14
	v_div_fmas_f32 v14, v14, v18, v16
	v_div_fixup_f32 v2, v14, v2, v35
	v_pk_mul_f32 v[2:3], v[4:5], v[2:3]
	v_bfe_u32 v14, v7, 16, 1
	v_bfe_u32 v4, v3, 16, 1
	v_bfe_u32 v5, v2, 16, 1
	v_bfe_u32 v15, v6, 16, 1
	v_add3_u32 v6, v6, v15, s33
	v_add3_u32 v7, v7, v14, s33
	v_add3_u32 v2, v2, v5, s33
	v_add3_u32 v3, v3, v4, s33
	v_bfe_u32 v4, v20, 16, 1
	v_bfe_u32 v5, v21, 16, 1
	v_bfe_u32 v14, v8, 16, 1
	v_bfe_u32 v15, v9, 16, 1
	v_add3_u32 v9, v9, v15, s33
	v_add3_u32 v8, v8, v14, s33
	v_add3_u32 v5, v21, v5, s33
	v_add3_u32 v4, v20, v4, s33
	v_lshrrev_b32_e32 v14, 16, v4
	v_lshrrev_b32_e32 v15, 16, v5
	v_lshrrev_b32_e32 v4, 16, v8
	v_lshrrev_b32_e32 v5, 16, v9
	v_and_or_b32 v5, v3, s34, v5
	v_and_or_b32 v4, v2, s34, v4
	v_and_or_b32 v3, v7, s34, v15
	v_and_or_b32 v2, v6, s34, v14
	v_lshlrev_b64 v[6:7], 11, v[60:61]
	v_lshl_add_u64 v[6:7], s[68:69], 0, v[6:7]
	v_lshl_add_u64 v[6:7], v[6:7], 0, s[70:71]
	v_lshl_add_u64 v[6:7], v[6:7], 0, v[42:43]
	v_lshl_add_u64 v[8:9], v[6:7], 0, s[74:75]
	v_add_co_u32_e32 v6, vcc, 0xdc00000, v6
	s_nop 1
	v_addc_co_u32_e32 v7, vcc, 0, v7, vcc
	global_store_dwordx4 v[6:7], v[10:13], off offset:1024
	global_store_dwordx4 v[8:9], v[2:5], off offset:16
	s_branch .LBB0_2949

.LBB0_3084:
	s_or_b64 exec, exec, s[10:11]
	v_mov_b32_e32 v1, v0
	v_mov_b64_e32 v[2:3], s[0:1]
	s_barrier
	global_load_dwordx2 v[2:3], v[2:3], off offset:88 sc0 sc1
	s_waitcnt vmcnt(0)
	v_readfirstlane_b32 s5, v1
	s_ashr_i32 s5, s5, 4
	s_and_b32 s6, s5, -4
	s_cmp_gt_i32 s6, 63
	s_cbranch_scc1 .LBB0_3087
	v_and_b32_e32 v21, 63, v1
	v_mov_b32_e32 v91, 0
	v_lshlrev_b32_e32 v90, 4, v21
	s_waitcnt lgkmcnt(0)
	v_lshl_add_u64 v[2:3], v[2:3], 0, v[90:91]
	s_movk_i32 s5, 0x2000
	v_add_co_u32_e32 v18, vcc, s5, v2
	v_mbcnt_lo_u32_b32 v1, -1, 0
	s_nop 0
	v_addc_co_u32_e32 v19, vcc, 0, v3, vcc
	global_load_dwordx4 v[2:5], v[18:19], off
	global_load_dwordx4 v[6:9], v[18:19], off offset:1024
	global_load_dwordx4 v[10:13], v[18:19], off offset:2048
	global_load_dwordx4 v[14:17], v[18:19], off offset:3072
	v_mbcnt_hi_u32_b32 v18, -1, v1
	v_and_b32_e32 v1, 64, v18
	v_add_u32_e32 v19, 64, v1
	v_xor_b32_e32 v1, 1, v18
	v_cmp_lt_i32_e32 vcc, v1, v19
	v_xor_b32_e32 v20, 2, v18
	s_lshl_b32 s7, s28, 8
	v_cndmask_b32_e32 v1, v18, v1, vcc
	v_cmp_lt_i32_e32 vcc, v20, v19
	s_lshl_b32 s4, s4, 6
	s_add_i32 s8, s7, s4
	v_cndmask_b32_e32 v20, v18, v20, vcc
	v_lshlrev_b32_e32 v166, 2, v20
	v_xor_b32_e32 v20, 4, v18
	v_cmp_lt_i32_e32 vcc, v20, v19
	s_add_i32 s10, s6, s8
	s_add_u32 s4, s68, 0x5800000
	v_cndmask_b32_e32 v20, v18, v20, vcc
	v_lshlrev_b32_e32 v167, 2, v20
	v_xor_b32_e32 v20, 8, v18
	v_cmp_lt_i32_e32 vcc, v20, v19
	s_addc_u32 s5, s69, 0
	s_lshl_b32 s3, s3, 6
	v_cndmask_b32_e32 v20, v18, v20, vcc
	v_lshlrev_b32_e32 v168, 2, v20
	v_xor_b32_e32 v20, 16, v18
	v_cmp_lt_i32_e32 vcc, v20, v19
	s_add_i32 s3, s7, s3
	s_add_i32 s3, s3, s6
	v_cndmask_b32_e32 v20, v18, v20, vcc
	v_lshlrev_b32_e32 v169, 2, v20
	v_xor_b32_e32 v20, 32, v18
	v_cmp_lt_i32_e32 vcc, v20, v19
	s_lshl_b32 s2, s2, 6
	s_sub_i32 s2, s3, s2
	v_cndmask_b32_e32 v18, v18, v20, vcc
	s_ashr_i32 s11, s10, 31
	v_lshlrev_b32_e32 v170, 2, v18
	v_lshlrev_b32_e32 v18, 2, v21
	s_or_b32 s20, s8, 32
	s_sub_i32 s8, s2, 32
	s_lshl_b64 s[2:3], s[10:11], 11
	v_or_b32_e32 v20, 0x100, v18
	v_or_b32_e32 v22, 0x200, v18
	v_or_b32_e32 v24, 0x300, v18
	v_lshl_or_b32 v92, v21, 3, s2
	v_mov_b32_e32 v93, s3
	s_lshl_b64 s[2:3], s[10:11], 12
	v_lshlrev_b32_e32 v1, 2, v1
	v_or_b32_e32 v94, s2, v90
	v_mov_b32_e32 v95, s3
	v_mov_b32_e32 v171, 0x358637bd
	s_mov_b32 s2, 0xf800000
	v_mov_b32_e32 v172, 0x260
	v_lshlrev_b32_e32 v90, 2, v18
	s_movk_i32 s3, 0x7fff
	s_mov_b32 s21, 0xffff0000
	s_mov_b32 s22, 0xba00000
	v_lshlrev_b32_e32 v96, 2, v20
	v_lshlrev_b32_e32 v98, 2, v22
	v_mov_b32_e32 v99, v91
	v_lshlrev_b32_e32 v100, 2, v24
	v_mov_b32_e32 v101, v91
	s_mov_b32 s23, 0xba01000
	s_mov_b64 s[12:13], 0x10000
	s_mov_b64 s[14:15], 0x20000
	v_mov_b32_e32 v97, v91
.LBB0_3086:
	v_lshl_add_u64 v[18:19], s[68:69], 0, v[94:95]
	v_lshl_add_u64 v[22:23], s[68:69], 0, v[92:93]
	v_add_co_u32_e32 v20, vcc, 0x7800000, v18
	v_add_co_u32_e64 v102, s[6:7], s22, v22
	s_nop 0
	v_addc_co_u32_e32 v21, vcc, 0, v19, vcc
	v_addc_co_u32_e64 v103, s[6:7], 0, v23, s[6:7]
	v_add_co_u32_e64 v104, s[6:7], s23, v22
	v_add_co_u32_e32 v22, vcc, 0x7801000, v18
	s_nop 0
	v_addc_co_u32_e64 v105, s[6:7], 0, v23, s[6:7]
	global_load_dwordx4 v[78:81], v[20:21], off
	global_load_dwordx4 v[74:77], v[20:21], off offset:1024
	global_load_dwordx4 v[70:73], v[20:21], off offset:2048
	global_load_dwordx4 v[66:69], v[20:21], off offset:3072
	v_addc_co_u32_e32 v23, vcc, 0, v19, vcc
	v_add_co_u32_e32 v20, vcc, 0x7802000, v18
	global_load_dwordx4 v[62:65], v[22:23], off
	global_load_dwordx4 v[58:61], v[22:23], off offset:1024
	global_load_dwordx4 v[54:57], v[22:23], off offset:2048
	global_load_dwordx4 v[50:53], v[22:23], off offset:3072
	v_addc_co_u32_e32 v21, vcc, 0, v19, vcc
	v_add_co_u32_e32 v82, vcc, 0x7803000, v18
	global_load_dwordx4 v[46:49], v[20:21], off
	global_load_dwordx4 v[42:45], v[20:21], off offset:1024
	global_load_dwordx4 v[38:41], v[20:21], off offset:2048
	global_load_dwordx4 v[34:37], v[20:21], off offset:3072
	v_addc_co_u32_e32 v83, vcc, 0, v19, vcc
	global_load_dwordx4 v[30:33], v[82:83], off
	global_load_dwordx4 v[26:29], v[82:83], off offset:1024
	global_load_dwordx4 v[22:25], v[82:83], off offset:2048
	global_load_dwordx4 v[18:21], v[82:83], off offset:3072
	s_add_i32 s24, s8, 32
	s_add_i32 s10, s8, 0xffffc022
	s_ashr_i32 s9, s24, 13
	s_cmpk_lt_i32 s24, 0x4000
	s_cselect_b32 s6, s9, s10
	s_mul_hi_i32 s7, s6, 0x9000
	s_mul_i32 s6, s6, 0x9000
	s_add_u32 s10, s4, s6
	s_addc_u32 s11, s5, s7
	s_add_u32 s6, s10, 0x6000
	s_addc_u32 s7, s11, 0
	s_add_u32 s10, s10, 0x7000
	s_addc_u32 s11, s11, 0
	v_lshl_add_u64 v[82:83], s[6:7], 0, v[90:91]
	v_lshl_add_u64 v[86:87], s[10:11], 0, v[90:91]
	global_load_dwordx4 v[82:85], v[82:83], off
	v_lshl_add_u64 v[148:149], s[6:7], 0, v[96:97]
	global_load_dwordx4 v[86:89], v[86:87], off
	v_lshl_add_u64 v[142:143], s[6:7], 0, v[98:99]
	v_lshl_add_u64 v[134:135], s[6:7], 0, v[100:101]
	s_add_i32 s6, s8, 0xffffc023
	s_cmpk_lt_i32 s24, 0x3fff
	s_cselect_b32 s6, s9, s6
	s_mul_hi_i32 s7, s6, 0x9000
	s_mul_i32 s6, s6, 0x9000
	v_lshl_add_u64 v[152:153], s[10:11], 0, v[96:97]
	v_lshl_add_u64 v[146:147], s[10:11], 0, v[98:99]
	v_lshl_add_u64 v[140:141], s[10:11], 0, v[100:101]
	s_add_u32 s10, s4, s6
	s_addc_u32 s11, s5, s7
	s_add_u32 s6, s10, 0x6000
	s_addc_u32 s7, s11, 0
	s_add_u32 s10, s10, 0x7000
	v_lshl_add_u64 v[132:133], s[6:7], 0, v[90:91]
	v_lshl_add_u64 v[126:127], s[6:7], 0, v[96:97]
	v_lshl_add_u64 v[118:119], s[6:7], 0, v[98:99]
	v_lshl_add_u64 v[114:115], s[6:7], 0, v[100:101]
	s_addc_u32 s11, s11, 0
	s_add_i32 s6, s8, 0xffffc024
	s_cmpk_lt_i32 s24, 0x3ffe
	s_cselect_b32 s6, s9, s6
	s_mul_hi_i32 s7, s6, 0x9000
	s_mul_i32 s6, s6, 0x9000
	s_add_u32 s6, s4, s6
	s_addc_u32 s7, s5, s7
	v_lshl_add_u64 v[138:139], s[10:11], 0, v[90:91]
	v_lshl_add_u64 v[130:131], s[10:11], 0, v[96:97]
	v_lshl_add_u64 v[124:125], s[10:11], 0, v[98:99]
	v_lshl_add_u64 v[116:117], s[10:11], 0, v[100:101]
	s_add_u32 s10, s6, 0x6000
	s_addc_u32 s11, s7, 0
	s_add_u32 s6, s6, 0x7000
	s_addc_u32 s7, s7, 0
	s_addk_i32 s8, 0xc025
	s_cmpk_lt_i32 s24, 0x3ffd
	v_lshl_add_u64 v[156:157], s[6:7], 0, v[90:91]
	v_lshl_add_u64 v[154:155], s[6:7], 0, v[96:97]
	v_lshl_add_u64 v[150:151], s[6:7], 0, v[98:99]
	v_lshl_add_u64 v[136:137], s[6:7], 0, v[100:101]
	s_cselect_b32 s6, s9, s8
	s_mul_hi_i32 s7, s6, 0x9000
	s_mul_i32 s6, s6, 0x9000
	s_add_u32 s6, s4, s6
	s_waitcnt vmcnt(0) lgkmcnt(0)
	v_pk_mul_f32 v[158:159], v[80:81], v[80:81]
	v_pk_mul_f32 v[160:161], v[78:79], v[78:79]
	v_pk_mul_f32 v[162:163], v[76:77], v[76:77]
	v_pk_mul_f32 v[164:165], v[74:75], v[74:75]
	v_mul_f32_e32 v174, v71, v71
	v_mul_f32_e32 v176, v73, v73
	v_mul_f32_e32 v187, v68, v68
	v_mul_f32_e32 v189, v69, v69
	v_pk_mov_b32 v[178:179], v[160:161], v[158:159] op_sel:[1,0]
	v_mov_b32_e32 v161, v159
	v_pk_mov_b32 v[158:159], v[164:165], v[162:163] op_sel:[1,0]
	v_mov_b32_e32 v165, v163
	v_pk_fma_f32 v[162:163], v[70:71], v[70:71], v[174:175] op_sel_hi:[1,1,0]
	v_pk_fma_f32 v[174:175], v[72:73], v[72:73], v[176:177] op_sel_hi:[1,1,0]
	v_pk_mul_f32 v[176:177], v[64:65], v[64:65]
	v_pk_mul_f32 v[180:181], v[62:63], v[62:63]
	v_pk_mul_f32 v[182:183], v[60:61], v[60:61]
	v_pk_mul_f32 v[184:185], v[58:59], v[58:59]
	v_mul_f32_e32 v186, v55, v55
	v_mul_f32_e32 v188, v57, v57
	v_pk_add_f32 v[160:161], v[178:179], v[160:161]
	v_pk_add_f32 v[158:159], v[158:159], v[164:165]
	v_mov_b32_e32 v163, v187
	v_mov_b32_e32 v175, v189
	v_pk_mov_b32 v[164:165], v[180:181], v[176:177] op_sel:[1,0]
	v_mov_b32_e32 v181, v177
	v_pk_mov_b32 v[176:177], v[184:185], v[182:183] op_sel:[1,0]
	v_mov_b32_e32 v185, v183
	v_pk_fma_f32 v[178:179], v[54:55], v[54:55], v[186:187] op_sel_hi:[1,1,0]
	v_pk_fma_f32 v[182:183], v[56:57], v[56:57], v[188:189] op_sel_hi:[1,1,0]
	v_pk_mul_f32 v[186:187], v[48:49], v[48:49]
	v_pk_mul_f32 v[188:189], v[46:47], v[46:47]
	v_pk_mul_f32 v[190:191], v[44:45], v[44:45]
	v_pk_mul_f32 v[192:193], v[42:43], v[42:43]
	v_mul_f32_e32 v173, v66, v66
	v_mul_f32_e32 v197, v67, v67
	v_mul_f32_e32 v195, v52, v52
	v_mul_f32_e32 v202, v53, v53
	v_mul_f32_e32 v194, v39, v39
	v_mul_f32_e32 v196, v41, v41
	v_pk_add_f32 v[198:199], v[160:161], v[160:161] op_sel:[0,1] op_sel_hi:[1,0]
	v_pk_add_f32 v[200:201], v[158:159], v[158:159] op_sel:[0,1] op_sel_hi:[1,0]
	v_pk_add_f32 v[174:175], v[162:163], v[174:175]
	v_pk_add_f32 v[158:159], v[164:165], v[180:181]
	v_pk_add_f32 v[160:161], v[176:177], v[184:185]
	v_pk_mov_b32 v[162:163], v[188:189], v[186:187] op_sel:[1,0]
	v_mov_b32_e32 v189, v187
	v_pk_mov_b32 v[164:165], v[192:193], v[190:191] op_sel:[1,0]
	v_mov_b32_e32 v193, v191
	v_mul_f32_e32 v203, v50, v50
	v_mul_f32_e32 v208, v51, v51
	v_mul_f32_e32 v211, v36, v36
	v_mul_f32_e32 v212, v37, v37
	v_mov_b32_e32 v179, v195
	v_mov_b32_e32 v183, v202
	v_pk_fma_f32 v[176:177], v[38:39], v[38:39], v[194:195] op_sel_hi:[1,1,0]
	v_pk_fma_f32 v[180:181], v[40:41], v[40:41], v[196:197] op_sel_hi:[1,1,0]
	v_pk_mul_f32 v[184:185], v[32:33], v[32:33]
	v_pk_mul_f32 v[186:187], v[30:31], v[30:31]
	v_pk_mul_f32 v[190:191], v[28:29], v[28:29]
	v_pk_mul_f32 v[194:195], v[26:27], v[26:27]
	v_mov_b32_e32 v199, v173
	v_mov_b32_e32 v201, v197
	v_pk_add_f32 v[204:205], v[158:159], v[158:159] op_sel:[0,1] op_sel_hi:[1,0]
	v_pk_add_f32 v[206:207], v[160:161], v[160:161] op_sel:[0,1] op_sel_hi:[1,0]
	v_pk_add_f32 v[162:163], v[162:163], v[188:189]
	v_pk_add_f32 v[164:165], v[164:165], v[192:193]
	v_mul_f32_e32 v209, v34, v34
	v_mul_f32_e32 v210, v35, v35
	v_pk_add_f32 v[178:179], v[178:179], v[182:183]
	v_mov_b32_e32 v177, v211
	v_mov_b32_e32 v181, v212
	v_pk_mov_b32 v[182:183], v[186:187], v[184:185] op_sel:[1,0]
	v_mov_b32_e32 v187, v185
	v_pk_mov_b32 v[184:185], v[194:195], v[190:191] op_sel:[1,0]
	v_mov_b32_e32 v195, v191
	v_pk_add_f32 v[188:189], v[198:199], v[200:201]
	v_mov_b32_e32 v205, v203
	v_mov_b32_e32 v207, v208
	v_pk_add_f32 v[190:191], v[162:163], v[162:163] op_sel:[0,1] op_sel_hi:[1,0]
	v_pk_add_f32 v[192:193], v[164:165], v[164:165] op_sel:[0,1] op_sel_hi:[1,0]
	v_pk_add_f32 v[176:177], v[176:177], v[180:181]
	v_pk_add_f32 v[174:175], v[188:189], v[174:175]
	v_pk_add_f32 v[180:181], v[204:205], v[206:207]
	v_mov_b32_e32 v191, v209
	v_mov_b32_e32 v193, v210
	v_add_f32_e32 v173, v174, v175
	v_pk_add_f32 v[174:175], v[180:181], v[178:179]
	v_pk_add_f32 v[178:179], v[190:191], v[192:193]
	v_add_f32_e32 v180, v174, v175
	v_pk_add_f32 v[174:175], v[178:179], v[176:177]
	ds_bpermute_b32 v176, v1, v173
	v_add_f32_e32 v174, v174, v175
	ds_bpermute_b32 v175, v1, v180
	ds_bpermute_b32 v177, v1, v174
	s_addc_u32 s7, s5, s7
	s_waitcnt lgkmcnt(2)
	v_add_f32_e32 v173, v173, v176
	ds_bpermute_b32 v176, v166, v173
	s_waitcnt lgkmcnt(2)
	v_add_f32_e32 v175, v180, v175
	ds_bpermute_b32 v178, v166, v175
	s_waitcnt lgkmcnt(2)
	v_add_f32_e32 v174, v174, v177
	ds_bpermute_b32 v177, v166, v174
	s_waitcnt lgkmcnt(2)
	v_add_f32_e32 v173, v173, v176
	ds_bpermute_b32 v176, v167, v173
	s_waitcnt lgkmcnt(2)
	v_add_f32_e32 v175, v175, v178
	ds_bpermute_b32 v178, v167, v175
	s_waitcnt lgkmcnt(2)
	v_add_f32_e32 v174, v174, v177
	ds_bpermute_b32 v177, v167, v174
	s_waitcnt lgkmcnt(2)
	v_add_f32_e32 v173, v173, v176
	ds_bpermute_b32 v176, v168, v173
	s_waitcnt lgkmcnt(2)
	v_add_f32_e32 v175, v175, v178
	ds_bpermute_b32 v178, v168, v175
	s_waitcnt lgkmcnt(2)
	v_add_f32_e32 v174, v174, v177
	ds_bpermute_b32 v177, v168, v174
	s_waitcnt lgkmcnt(2)
	v_add_f32_e32 v173, v173, v176
	ds_bpermute_b32 v176, v169, v173
	s_waitcnt lgkmcnt(2)
	v_add_f32_e32 v175, v175, v178
	ds_bpermute_b32 v178, v169, v175
	s_waitcnt lgkmcnt(2)
	v_add_f32_e32 v174, v174, v177
	ds_bpermute_b32 v177, v169, v174
	s_waitcnt lgkmcnt(2)
	v_add_f32_e32 v173, v173, v176
	ds_bpermute_b32 v176, v170, v173
	s_waitcnt lgkmcnt(2)
	v_add_f32_e32 v175, v175, v178
	ds_bpermute_b32 v178, v170, v175
	s_waitcnt lgkmcnt(2)
	v_add_f32_e32 v174, v174, v177
	ds_bpermute_b32 v177, v170, v174
	s_waitcnt lgkmcnt(2)
	v_add_f32_e32 v173, v173, v176
	s_add_u32 s16, s6, 0x6000
	v_fmamk_f32 v173, v173, 0x3a800000, v171
	s_addc_u32 s17, s7, 0
	s_waitcnt lgkmcnt(1)
	v_add_f32_e32 v175, v175, v178
	v_mul_f32_e32 v176, 0x4f800000, v173
	v_cmp_gt_f32_e32 vcc, s2, v173
	s_add_u32 s18, s6, 0x7000
	v_fmamk_f32 v175, v175, 0x3a800000, v171
	v_cndmask_b32_e32 v173, v173, v176, vcc
	s_addc_u32 s19, s7, 0
	s_waitcnt lgkmcnt(0)
	v_add_f32_e32 v174, v174, v177
	v_mul_f32_e32 v176, 0x4f800000, v175
	v_cmp_gt_f32_e64 s[6:7], s2, v175
	v_sqrt_f32_e32 v177, v173
	v_fmamk_f32 v174, v174, 0x3a800000, v171
	v_cndmask_b32_e64 v175, v175, v176, s[6:7]
	v_mul_f32_e32 v176, 0x4f800000, v174
	v_cmp_gt_f32_e64 s[8:9], s2, v174
	v_sqrt_f32_e32 v178, v175
	v_add_u32_e32 v179, -1, v177
	v_cndmask_b32_e64 v174, v174, v176, s[8:9]
	v_sqrt_f32_e32 v176, v174
	v_add_u32_e32 v180, 1, v177
	v_fma_f32 v181, -v179, v177, v173
	v_lshl_add_u64 v[112:113], s[10:11], 0, v[90:91]
	v_lshl_add_u64 v[106:107], s[10:11], 0, v[96:97]
	v_lshl_add_u64 v[108:109], s[10:11], 0, v[98:99]
	v_lshl_add_u64 v[110:111], s[10:11], 0, v[100:101]
	v_pk_add_f32 v[162:163], v[182:183], v[186:187]
	v_fma_f32 v182, -v180, v177, v173
	v_add_u32_e32 v183, -1, v178
	v_cmp_ge_f32_e64 s[10:11], 0, v181
	v_pk_add_f32 v[164:165], v[184:185], v[194:195]
	v_add_u32_e32 v184, 1, v178
	v_cndmask_b32_e64 v177, v177, v179, s[10:11]
	v_fma_f32 v179, -v183, v178, v175
	v_cmp_lt_f32_e64 s[10:11], 0, v182
	v_fma_f32 v181, -v184, v178, v175
	v_add_u32_e32 v185, -1, v176
	v_cndmask_b32_e64 v177, v177, v180, s[10:11]
	v_cmp_ge_f32_e64 s[10:11], 0, v179
	v_add_u32_e32 v186, 1, v176
	v_fma_f32 v179, -v185, v176, v174
	v_cndmask_b32_e64 v178, v178, v183, s[10:11]
	v_cmp_lt_f32_e64 s[10:11], 0, v181
	v_fma_f32 v180, -v186, v176, v174
	v_mul_f32_e32 v181, 0x37800000, v177
	v_cndmask_b32_e64 v178, v178, v184, s[10:11]
	v_cmp_ge_f32_e64 s[10:11], 0, v179
	v_cndmask_b32_e32 v177, v177, v181, vcc
	v_cmp_class_f32_e32 vcc, v173, v172
	v_cndmask_b32_e64 v176, v176, v185, s[10:11]
	v_cmp_lt_f32_e64 s[10:11], 0, v180
	v_mul_f32_e32 v179, 0x37800000, v178
	v_cndmask_b32_e32 v173, v177, v173, vcc
	v_cndmask_b32_e64 v176, v176, v186, s[10:11]
	v_cndmask_b32_e64 v177, v178, v179, s[6:7]
	v_cmp_class_f32_e32 vcc, v175, v172
	v_mul_f32_e32 v178, 0x37800000, v176
	v_div_scale_f32 v179, s[6:7], v173, v173, 1.0
	v_cndmask_b32_e32 v175, v177, v175, vcc
	v_cndmask_b32_e64 v176, v176, v178, s[8:9]
	v_cmp_class_f32_e32 vcc, v174, v172
	v_rcp_f32_e32 v177, v179
	v_div_scale_f32 v178, s[8:9], v175, v175, 1.0
	v_cndmask_b32_e32 v176, v176, v174, vcc
	v_rcp_f32_e32 v182, v178
	v_div_scale_f32 v183, s[10:11], v176, v176, 1.0
	v_rcp_f32_e32 v185, v183
	v_fma_f32 v174, -v179, v177, 1.0
	v_div_scale_f32 v180, s[6:7], 1.0, v173, 1.0
	v_fmac_f32_e32 v177, v174, v177
	v_fma_f32 v174, -v178, v182, 1.0
	v_mul_f32_e32 v186, v180, v177
	v_div_scale_f32 v181, s[8:9], 1.0, v175, 1.0
	v_fmac_f32_e32 v182, v174, v182
	v_fma_f32 v174, -v183, v185, 1.0
	v_fma_f32 v187, -v179, v186, v180
	v_div_scale_f32 v184, s[10:11], 1.0, v176, 1.0
	v_mul_f32_e32 v188, v181, v182
	v_fmac_f32_e32 v185, v174, v185
	v_fmac_f32_e32 v186, v187, v177
	v_fma_f32 v174, -v178, v188, v181
	v_mul_f32_e32 v187, v184, v185
	v_fma_f32 v179, -v179, v186, v180
	s_mov_b64 vcc, s[6:7]
	v_fmac_f32_e32 v188, v174, v182
	v_fma_f32 v174, -v183, v187, v184
	v_div_fmas_f32 v177, v179, v177, v186
	v_fma_f32 v178, -v178, v188, v181
	v_fmac_f32_e32 v187, v174, v185
	v_div_fixup_f32 v174, v177, v173, 1.0
	s_mov_b64 vcc, s[8:9]
	v_div_fmas_f32 v173, v178, v182, v188
	v_fma_f32 v177, -v183, v187, v184
	v_pk_mul_f32 v[80:81], v[80:81], v[174:175] op_sel_hi:[1,0]
	v_pk_mul_f32 v[78:79], v[78:79], v[174:175] op_sel_hi:[1,0]
	s_mov_b64 vcc, s[10:11]
	v_pk_add_f32 v[88:89], v[88:89], 1.0 op_sel_hi:[1,0]
	v_pk_add_f32 v[86:87], v[86:87], 1.0 op_sel_hi:[1,0]
	v_pk_mul_f32 v[76:77], v[76:77], v[174:175] op_sel_hi:[1,0]
	v_pk_mul_f32 v[74:75], v[74:75], v[174:175] op_sel_hi:[1,0]
	v_pk_mul_f32 v[72:73], v[72:73], v[174:175] op_sel_hi:[1,0]
	v_pk_mul_f32 v[70:71], v[70:71], v[174:175] op_sel_hi:[1,0]
	v_pk_mul_f32 v[68:69], v[68:69], v[174:175] op_sel_hi:[1,0]
	v_pk_mul_f32 v[66:67], v[66:67], v[174:175] op_sel_hi:[1,0]
	v_div_fixup_f32 v174, v173, v175, 1.0
	v_div_fmas_f32 v173, v177, v185, v187
	v_pk_mul_f32 v[78:79], v[2:3], v[78:79]
	v_pk_mul_f32 v[80:81], v[4:5], v[80:81]
	v_pk_mul_f32 v[64:65], v[64:65], v[174:175] op_sel_hi:[1,0]
	v_pk_mul_f32 v[62:63], v[62:63], v[174:175] op_sel_hi:[1,0]
	v_pk_mul_f32 v[60:61], v[60:61], v[174:175] op_sel_hi:[1,0]
	v_pk_mul_f32 v[58:59], v[58:59], v[174:175] op_sel_hi:[1,0]
	v_pk_mul_f32 v[56:57], v[56:57], v[174:175] op_sel_hi:[1,0]
	v_pk_mul_f32 v[54:55], v[54:55], v[174:175] op_sel_hi:[1,0]
	v_pk_mul_f32 v[52:53], v[52:53], v[174:175] op_sel_hi:[1,0]
	v_pk_mul_f32 v[174:175], v[50:51], v[174:175] op_sel_hi:[1,0]
	v_div_fixup_f32 v50, v173, v176, 1.0
	v_pk_fma_f32 v[80:81], v[88:89], v[80:81], v[84:85]
	v_pk_fma_f32 v[78:79], v[86:87], v[78:79], v[82:83]
	v_pk_mul_f32 v[86:87], v[16:17], v[52:53]
	v_pk_mul_f32 v[48:49], v[48:49], v[50:51] op_sel_hi:[1,0]
	v_pk_mul_f32 v[46:47], v[46:47], v[50:51] op_sel_hi:[1,0]
	v_bfe_u32 v51, v78, 16, 1
	v_bfe_u32 v53, v80, 16, 1
	v_pk_mul_f32 v[82:83], v[10:11], v[54:55]
	v_pk_mul_f32 v[84:85], v[14:15], v[174:175]
	v_bfe_u32 v52, v79, 16, 1
	v_bfe_u32 v54, v81, 16, 1
	v_pk_mul_f32 v[88:89], v[2:3], v[46:47]
	v_pk_mul_f32 v[174:175], v[4:5], v[48:49]
	v_add3_u32 v46, v78, v51, s3
	v_add3_u32 v48, v80, v53, s3
	v_add3_u32 v47, v79, v52, s3
	v_add3_u32 v49, v81, v54, s3
	v_lshrrev_b32_e32 v46, 16, v46
	v_lshrrev_b32_e32 v48, 16, v48
	v_and_or_b32 v46, v47, s21, v46
	v_and_or_b32 v47, v49, s21, v48
	global_store_dwordx2 v[102:103], v[46:47], off
	global_load_dwordx4 v[46:49], v[152:153], off
	s_nop 0
	global_load_dwordx4 v[52:55], v[148:149], off
	v_pk_mul_f32 v[74:75], v[6:7], v[74:75]
	v_pk_mul_f32 v[76:77], v[8:9], v[76:77]
	v_pk_mul_f32 v[70:71], v[10:11], v[70:71]
	v_pk_mul_f32 v[72:73], v[12:13], v[72:73]
	v_pk_mul_f32 v[66:67], v[66:67], v[14:15]
	v_pk_mul_f32 v[68:69], v[68:69], v[16:17]
	v_pk_mul_f32 v[62:63], v[2:3], v[62:63]
	v_pk_mul_f32 v[64:65], v[4:5], v[64:65]
	v_pk_mul_f32 v[58:59], v[6:7], v[58:59]
	v_pk_mul_f32 v[60:61], v[8:9], v[60:61]
	v_pk_mul_f32 v[56:57], v[12:13], v[56:57]
	v_mul_f32_e32 v196, v23, v23
	v_mul_f32_e32 v202, v25, v25
	v_mul_f32_e32 v213, v18, v18
	v_mul_f32_e32 v214, v19, v19
	v_mul_f32_e32 v215, v20, v20
	v_mul_f32_e32 v216, v21, v21
	v_pk_fma_f32 v[158:159], v[22:23], v[22:23], v[196:197] op_sel_hi:[1,1,0]
	v_pk_fma_f32 v[160:161], v[24:25], v[24:25], v[202:203] op_sel_hi:[1,1,0]
	v_mov_b32_e32 v159, v215
	v_mov_b32_e32 v161, v216
	v_lshl_add_u64 v[144:145], s[18:19], 0, v[90:91]
	v_lshl_add_u64 v[128:129], s[16:17], 0, v[90:91]
	v_lshl_add_u64 v[122:123], s[18:19], 0, v[96:97]
	v_lshl_add_u64 v[120:121], s[16:17], 0, v[96:97]
	v_lshl_add_u64 v[92:93], v[92:93], 0, s[12:13]
	v_lshl_add_u64 v[94:95], v[94:95], 0, s[14:15]
	s_mov_b32 s8, s24
	s_cmp_lt_i32 s24, s20
	s_waitcnt vmcnt(0) lgkmcnt(0)
	v_pk_add_f32 v[48:49], v[48:49], 1.0 op_sel_hi:[1,0]
	v_pk_add_f32 v[46:47], v[46:47], 1.0 op_sel_hi:[1,0]
	v_pk_fma_f32 v[48:49], v[48:49], v[76:77], v[54:55]
	v_pk_fma_f32 v[46:47], v[46:47], v[74:75], v[52:53]
	v_bfe_u32 v53, v48, 16, 1
	v_bfe_u32 v51, v46, 16, 1
	v_bfe_u32 v52, v47, 16, 1
	v_bfe_u32 v54, v49, 16, 1
	v_add3_u32 v46, v46, v51, s3
	v_add3_u32 v48, v48, v53, s3
	v_add3_u32 v47, v47, v52, s3
	v_add3_u32 v49, v49, v54, s3
	v_lshrrev_b32_e32 v46, 16, v46
	v_lshrrev_b32_e32 v48, 16, v48
	v_and_or_b32 v46, v47, s21, v46
	v_and_or_b32 v47, v49, s21, v48
	global_store_dwordx2 v[102:103], v[46:47], off offset:512
	global_load_dwordx4 v[46:49], v[146:147], off
	s_nop 0
	global_load_dwordx4 v[52:55], v[142:143], off
	s_waitcnt vmcnt(0) lgkmcnt(0)
	v_pk_add_f32 v[48:49], v[48:49], 1.0 op_sel_hi:[1,0]
	v_pk_add_f32 v[46:47], v[46:47], 1.0 op_sel_hi:[1,0]
	v_pk_fma_f32 v[48:49], v[72:73], v[48:49], v[54:55]
	v_pk_fma_f32 v[46:47], v[70:71], v[46:47], v[52:53]
	v_bfe_u32 v53, v48, 16, 1
	v_bfe_u32 v51, v46, 16, 1
	v_bfe_u32 v52, v47, 16, 1
	v_bfe_u32 v54, v49, 16, 1
	v_add3_u32 v46, v46, v51, s3
	v_add3_u32 v48, v48, v53, s3
	v_add3_u32 v47, v47, v52, s3
	v_add3_u32 v49, v49, v54, s3
	v_lshrrev_b32_e32 v46, 16, v46
	v_lshrrev_b32_e32 v48, 16, v48
	v_and_or_b32 v46, v47, s21, v46
	v_and_or_b32 v47, v49, s21, v48
	global_store_dwordx2 v[102:103], v[46:47], off offset:1024
	global_load_dwordx4 v[46:49], v[140:141], off
	s_nop 0
	global_load_dwordx4 v[52:55], v[134:135], off
	s_waitcnt vmcnt(0) lgkmcnt(0)
	v_pk_add_f32 v[48:49], v[48:49], 1.0 op_sel_hi:[1,0]
	v_pk_add_f32 v[46:47], v[46:47], 1.0 op_sel_hi:[1,0]
	v_pk_fma_f32 v[48:49], v[68:69], v[48:49], v[54:55]
	v_pk_fma_f32 v[46:47], v[66:67], v[46:47], v[52:53]
	v_bfe_u32 v53, v48, 16, 1
	v_bfe_u32 v51, v46, 16, 1
	v_bfe_u32 v52, v47, 16, 1
	v_bfe_u32 v54, v49, 16, 1
	v_add3_u32 v46, v46, v51, s3
	v_add3_u32 v48, v48, v53, s3
	v_add3_u32 v47, v47, v52, s3
	v_add3_u32 v49, v49, v54, s3
	v_lshrrev_b32_e32 v46, 16, v46
	v_lshrrev_b32_e32 v48, 16, v48
	v_and_or_b32 v46, v47, s21, v46
	v_and_or_b32 v47, v49, s21, v48
	global_store_dwordx2 v[102:103], v[46:47], off offset:1536
	global_load_dwordx4 v[46:49], v[138:139], off
	s_nop 0
	global_load_dwordx4 v[52:55], v[132:133], off
	s_waitcnt vmcnt(0) lgkmcnt(0)
	v_pk_add_f32 v[48:49], v[48:49], 1.0 op_sel_hi:[1,0]
	v_pk_add_f32 v[46:47], v[46:47], 1.0 op_sel_hi:[1,0]
	v_pk_fma_f32 v[48:49], v[48:49], v[64:65], v[54:55]
	v_pk_fma_f32 v[46:47], v[46:47], v[62:63], v[52:53]
	v_bfe_u32 v53, v48, 16, 1
	v_bfe_u32 v51, v46, 16, 1
	v_bfe_u32 v52, v47, 16, 1
	v_bfe_u32 v54, v49, 16, 1
	v_add3_u32 v46, v46, v51, s3
	v_add3_u32 v48, v48, v53, s3
	v_add3_u32 v47, v47, v52, s3
	v_add3_u32 v49, v49, v54, s3
	v_lshrrev_b32_e32 v46, 16, v46
	v_lshrrev_b32_e32 v48, 16, v48
	v_and_or_b32 v46, v47, s21, v46
	v_and_or_b32 v47, v49, s21, v48
	global_store_dwordx2 v[102:103], v[46:47], off offset:2048
	global_load_dwordx4 v[46:49], v[130:131], off
	s_nop 0
	global_load_dwordx4 v[52:55], v[126:127], off
	s_waitcnt vmcnt(0) lgkmcnt(0)
	v_pk_add_f32 v[48:49], v[48:49], 1.0 op_sel_hi:[1,0]
	v_pk_add_f32 v[46:47], v[46:47], 1.0 op_sel_hi:[1,0]
	v_pk_fma_f32 v[48:49], v[48:49], v[60:61], v[54:55]
	v_pk_fma_f32 v[46:47], v[46:47], v[58:59], v[52:53]
	v_bfe_u32 v53, v48, 16, 1
	v_bfe_u32 v51, v46, 16, 1
	v_bfe_u32 v52, v47, 16, 1
	v_bfe_u32 v54, v49, 16, 1
	v_add3_u32 v46, v46, v51, s3
	v_add3_u32 v48, v48, v53, s3
	v_add3_u32 v47, v47, v52, s3
	v_add3_u32 v49, v49, v54, s3
	v_lshrrev_b32_e32 v46, 16, v46
	v_lshrrev_b32_e32 v48, 16, v48
	v_and_or_b32 v46, v47, s21, v46
	v_and_or_b32 v47, v49, s21, v48
	global_store_dwordx2 v[102:103], v[46:47], off offset:2560
	global_load_dwordx4 v[46:49], v[124:125], off
	s_nop 0
	global_load_dwordx4 v[52:55], v[118:119], off
	v_pk_add_f32 v[58:59], v[164:165], v[164:165] op_sel:[0,1] op_sel_hi:[1,0]
	v_pk_add_f32 v[60:61], v[158:159], v[160:161]
	v_mov_b32_e32 v59, v214
	s_waitcnt vmcnt(0) lgkmcnt(0)
	v_pk_add_f32 v[48:49], v[48:49], 1.0 op_sel_hi:[1,0]
	v_pk_add_f32 v[46:47], v[46:47], 1.0 op_sel_hi:[1,0]
	v_pk_fma_f32 v[48:49], v[48:49], v[56:57], v[54:55]
	v_pk_fma_f32 v[46:47], v[46:47], v[82:83], v[52:53]
	v_bfe_u32 v53, v48, 16, 1
	v_bfe_u32 v51, v46, 16, 1
	v_bfe_u32 v52, v47, 16, 1
	v_bfe_u32 v54, v49, 16, 1
	v_add3_u32 v46, v46, v51, s3
	v_add3_u32 v48, v48, v53, s3
	v_add3_u32 v47, v47, v52, s3
	v_add3_u32 v49, v49, v54, s3
	v_lshrrev_b32_e32 v46, 16, v46
	v_lshrrev_b32_e32 v48, 16, v48
	v_and_or_b32 v46, v47, s21, v46
	v_and_or_b32 v47, v49, s21, v48
	global_store_dwordx2 v[102:103], v[46:47], off offset:3072
	global_load_dwordx4 v[46:49], v[116:117], off
	s_nop 0
	global_load_dwordx4 v[52:55], v[114:115], off
	v_pk_add_f32 v[56:57], v[162:163], v[162:163] op_sel:[0,1] op_sel_hi:[1,0]
	s_waitcnt vmcnt(0) lgkmcnt(0)
	v_pk_add_f32 v[48:49], v[48:49], 1.0 op_sel_hi:[1,0]
	v_pk_add_f32 v[46:47], v[46:47], 1.0 op_sel_hi:[1,0]
	v_pk_fma_f32 v[48:49], v[86:87], v[48:49], v[54:55]
	v_pk_fma_f32 v[46:47], v[84:85], v[46:47], v[52:53]
	v_bfe_u32 v53, v48, 16, 1
	v_bfe_u32 v51, v46, 16, 1
	v_bfe_u32 v52, v47, 16, 1
	v_bfe_u32 v54, v49, 16, 1
	v_add3_u32 v46, v46, v51, s3
	v_add3_u32 v48, v48, v53, s3
	v_add3_u32 v47, v47, v52, s3
	v_add3_u32 v49, v49, v54, s3
	v_lshrrev_b32_e32 v46, 16, v46
	v_lshrrev_b32_e32 v48, 16, v48
	v_and_or_b32 v46, v47, s21, v46
	v_and_or_b32 v47, v49, s21, v48
	global_store_dwordx2 v[102:103], v[46:47], off offset:3584
	global_load_dwordx4 v[46:49], v[156:157], off
	s_nop 0
	global_load_dwordx4 v[52:55], v[112:113], off
	v_mov_b32_e32 v57, v213
	s_waitcnt vmcnt(0) lgkmcnt(0)
	v_pk_add_f32 v[48:49], v[48:49], 1.0 op_sel_hi:[1,0]
	v_pk_add_f32 v[46:47], v[46:47], 1.0 op_sel_hi:[1,0]
	v_pk_fma_f32 v[48:49], v[48:49], v[174:175], v[54:55]
	v_pk_fma_f32 v[46:47], v[46:47], v[88:89], v[52:53]
	v_bfe_u32 v53, v48, 16, 1
	v_bfe_u32 v51, v46, 16, 1
	v_bfe_u32 v52, v47, 16, 1
	v_bfe_u32 v54, v49, 16, 1
	v_add3_u32 v46, v46, v51, s3
	v_add3_u32 v48, v48, v53, s3
	v_add3_u32 v47, v47, v52, s3
	v_add3_u32 v49, v49, v54, s3
	v_lshrrev_b32_e32 v46, 16, v46
	v_lshrrev_b32_e32 v48, 16, v48
	v_and_or_b32 v46, v47, s21, v46
	v_and_or_b32 v47, v49, s21, v48
	global_store_dwordx2 v[104:105], v[46:47], off
	global_load_dwordx4 v[46:49], v[154:155], off
	s_nop 0
	global_load_dwordx4 v[52:55], v[106:107], off
	v_pk_mul_f32 v[44:45], v[44:45], v[50:51] op_sel_hi:[1,0]
	v_pk_mul_f32 v[42:43], v[42:43], v[50:51] op_sel_hi:[1,0]
	v_pk_mul_f32 v[44:45], v[8:9], v[44:45]
	v_pk_mul_f32 v[42:43], v[6:7], v[42:43]
	s_waitcnt vmcnt(0) lgkmcnt(0)
	v_pk_add_f32 v[48:49], v[48:49], 1.0 op_sel_hi:[1,0]
	v_pk_add_f32 v[46:47], v[46:47], 1.0 op_sel_hi:[1,0]
	v_pk_fma_f32 v[44:45], v[48:49], v[44:45], v[54:55]
	v_pk_fma_f32 v[42:43], v[46:47], v[42:43], v[52:53]
	v_bfe_u32 v48, v44, 16, 1
	v_bfe_u32 v46, v42, 16, 1
	v_bfe_u32 v47, v43, 16, 1
	v_bfe_u32 v49, v45, 16, 1
	v_add3_u32 v42, v42, v46, s3
	v_add3_u32 v44, v44, v48, s3
	v_add3_u32 v43, v43, v47, s3
	v_add3_u32 v45, v45, v49, s3
	v_lshrrev_b32_e32 v42, 16, v42
	v_lshrrev_b32_e32 v44, 16, v44
	v_and_or_b32 v42, v43, s21, v42
	v_and_or_b32 v43, v45, s21, v44
	global_store_dwordx2 v[104:105], v[42:43], off offset:512
	global_load_dwordx4 v[42:45], v[150:151], off
	s_nop 0
	global_load_dwordx4 v[46:49], v[108:109], off
	v_pk_add_f32 v[52:53], v[56:57], v[58:59]
	s_waitcnt vmcnt(0) lgkmcnt(0)
	v_pk_add_f32 v[44:45], v[44:45], 1.0 op_sel_hi:[1,0]
	v_pk_add_f32 v[52:53], v[52:53], v[60:61]
	v_pk_add_f32 v[42:43], v[42:43], 1.0 op_sel_hi:[1,0]
	v_add_f32_e32 v51, v52, v53
	ds_bpermute_b32 v52, v1, v51
	s_waitcnt lgkmcnt(0)
	v_add_f32_e32 v51, v51, v52
	ds_bpermute_b32 v52, v166, v51
	s_waitcnt lgkmcnt(0)
	v_add_f32_e32 v51, v51, v52
	v_pk_mul_f32 v[40:41], v[40:41], v[50:51] op_sel_hi:[1,0]
	v_pk_mul_f32 v[38:39], v[38:39], v[50:51] op_sel_hi:[1,0]
	v_pk_mul_f32 v[40:41], v[12:13], v[40:41]
	v_pk_mul_f32 v[38:39], v[10:11], v[38:39]
	v_pk_fma_f32 v[40:41], v[44:45], v[40:41], v[48:49]
	v_pk_fma_f32 v[38:39], v[42:43], v[38:39], v[46:47]
	v_bfe_u32 v44, v40, 16, 1
	v_bfe_u32 v42, v38, 16, 1
	v_bfe_u32 v43, v39, 16, 1
	v_bfe_u32 v45, v41, 16, 1
	v_add3_u32 v38, v38, v42, s3
	v_add3_u32 v40, v40, v44, s3
	v_add3_u32 v39, v39, v43, s3
	v_add3_u32 v41, v41, v45, s3
	v_lshrrev_b32_e32 v38, 16, v38
	v_lshrrev_b32_e32 v40, 16, v40
	v_and_or_b32 v38, v39, s21, v38
	v_and_or_b32 v39, v41, s21, v40
	global_store_dwordx2 v[104:105], v[38:39], off offset:1024
	global_load_dwordx4 v[38:41], v[136:137], off
	s_nop 0
	global_load_dwordx4 v[42:45], v[110:111], off
	v_pk_mul_f32 v[36:37], v[36:37], v[50:51] op_sel_hi:[1,0]
	v_pk_mul_f32 v[34:35], v[34:35], v[50:51] op_sel_hi:[1,0]
	v_pk_mul_f32 v[36:37], v[16:17], v[36:37]
	v_pk_mul_f32 v[34:35], v[14:15], v[34:35]
	ds_bpermute_b32 v46, v167, v51
	s_waitcnt lgkmcnt(0)
	v_add_f32_e32 v46, v51, v46
	ds_bpermute_b32 v47, v168, v46
	s_waitcnt lgkmcnt(0)
	v_add_f32_e32 v46, v46, v47
	ds_bpermute_b32 v47, v169, v46
	s_waitcnt lgkmcnt(0)
	v_add_f32_e32 v46, v46, v47
	ds_bpermute_b32 v47, v170, v46
	s_waitcnt lgkmcnt(0)
	v_add_f32_e32 v46, v46, v47
	v_fmamk_f32 v46, v46, 0x3a800000, v171
	v_mul_f32_e32 v47, 0x4f800000, v46
	v_cmp_gt_f32_e32 vcc, s2, v46
	s_waitcnt vmcnt(0)
	v_pk_add_f32 v[40:41], v[40:41], 1.0 op_sel_hi:[1,0]
	v_pk_add_f32 v[38:39], v[38:39], 1.0 op_sel_hi:[1,0]
	v_pk_fma_f32 v[36:37], v[36:37], v[40:41], v[44:45]
	v_pk_fma_f32 v[34:35], v[34:35], v[38:39], v[42:43]
	v_bfe_u32 v40, v36, 16, 1
	v_bfe_u32 v38, v34, 16, 1
	v_bfe_u32 v39, v35, 16, 1
	v_bfe_u32 v41, v37, 16, 1
	v_add3_u32 v34, v34, v38, s3
	v_add3_u32 v36, v36, v40, s3
	v_add3_u32 v35, v35, v39, s3
	v_add3_u32 v37, v37, v41, s3
	v_lshrrev_b32_e32 v34, 16, v34
	v_lshrrev_b32_e32 v36, 16, v36
	v_and_or_b32 v34, v35, s21, v34
	v_and_or_b32 v35, v37, s21, v36
	global_store_dwordx2 v[104:105], v[34:35], off offset:1536
	global_load_dwordx4 v[34:37], v[144:145], off
	s_nop 0
	global_load_dwordx4 v[38:41], v[128:129], off
	v_cndmask_b32_e32 v42, v46, v47, vcc
	v_sqrt_f32_e32 v43, v42
	s_waitcnt vmcnt(0) lgkmcnt(0)
	v_pk_add_f32 v[36:37], v[36:37], 1.0 op_sel_hi:[1,0]
	v_add_u32_e32 v44, -1, v43
	v_add_u32_e32 v45, 1, v43
	v_fma_f32 v46, -v44, v43, v42
	v_fma_f32 v47, -v45, v43, v42
	v_cmp_ge_f32_e64 s[6:7], 0, v46
	v_pk_add_f32 v[34:35], v[34:35], 1.0 op_sel_hi:[1,0]
	s_nop 0
	v_cndmask_b32_e64 v43, v43, v44, s[6:7]
	v_cmp_lt_f32_e64 s[6:7], 0, v47
	s_nop 1
	v_cndmask_b32_e64 v43, v43, v45, s[6:7]
	v_mul_f32_e32 v44, 0x37800000, v43
	v_cndmask_b32_e32 v43, v43, v44, vcc
	v_cmp_class_f32_e32 vcc, v42, v172
	s_nop 1
	v_cndmask_b32_e32 v42, v43, v42, vcc
	v_div_scale_f32 v43, s[6:7], v42, v42, 1.0
	v_rcp_f32_e32 v45, v43
	v_div_scale_f32 v44, vcc, 1.0, v42, 1.0
	v_fma_f32 v46, -v43, v45, 1.0
	v_fmac_f32_e32 v45, v46, v45
	v_mul_f32_e32 v46, v44, v45
	v_fma_f32 v47, -v43, v46, v44
	v_fmac_f32_e32 v46, v47, v45
	v_fma_f32 v43, -v43, v46, v44
	v_div_fmas_f32 v43, v43, v45, v46
	v_div_fixup_f32 v42, v43, v42, 1.0
	v_pk_mul_f32 v[32:33], v[32:33], v[42:43] op_sel_hi:[1,0]
	v_pk_mul_f32 v[30:31], v[30:31], v[42:43] op_sel_hi:[1,0]
	v_pk_mul_f32 v[32:33], v[4:5], v[32:33]
	v_pk_mul_f32 v[30:31], v[2:3], v[30:31]
	v_pk_fma_f32 v[32:33], v[36:37], v[32:33], v[40:41]
	v_pk_fma_f32 v[30:31], v[34:35], v[30:31], v[38:39]
	v_bfe_u32 v36, v32, 16, 1
	v_bfe_u32 v34, v30, 16, 1
	v_bfe_u32 v35, v31, 16, 1
	v_bfe_u32 v37, v33, 16, 1
	v_add3_u32 v30, v30, v34, s3
	v_add3_u32 v32, v32, v36, s3
	v_add3_u32 v31, v31, v35, s3
	v_add3_u32 v33, v33, v37, s3
	v_lshrrev_b32_e32 v30, 16, v30
	v_lshrrev_b32_e32 v32, 16, v32
	v_and_or_b32 v30, v31, s21, v30
	v_and_or_b32 v31, v33, s21, v32
	global_store_dwordx2 v[104:105], v[30:31], off offset:2048
	global_load_dwordx4 v[30:33], v[122:123], off
	s_nop 0
	global_load_dwordx4 v[34:37], v[120:121], off
	v_pk_mul_f32 v[28:29], v[28:29], v[42:43] op_sel_hi:[1,0]
	v_pk_mul_f32 v[26:27], v[26:27], v[42:43] op_sel_hi:[1,0]
	v_pk_mul_f32 v[28:29], v[8:9], v[28:29]
	v_pk_mul_f32 v[26:27], v[6:7], v[26:27]
	v_lshl_add_u64 v[40:41], s[18:19], 0, v[98:99]
	v_lshl_add_u64 v[38:39], s[16:17], 0, v[98:99]
	v_pk_mul_f32 v[24:25], v[24:25], v[42:43] op_sel_hi:[1,0]
	v_pk_mul_f32 v[22:23], v[22:23], v[42:43] op_sel_hi:[1,0]
	v_pk_mul_f32 v[24:25], v[12:13], v[24:25]
	v_pk_mul_f32 v[22:23], v[10:11], v[22:23]
	v_pk_mul_f32 v[20:21], v[20:21], v[42:43] op_sel_hi:[1,0]
	v_pk_mul_f32 v[18:19], v[18:19], v[42:43] op_sel_hi:[1,0]
	v_pk_mul_f32 v[20:21], v[16:17], v[20:21]
	v_pk_mul_f32 v[18:19], v[14:15], v[18:19]
	s_waitcnt vmcnt(0) lgkmcnt(0)
	v_pk_add_f32 v[32:33], v[32:33], 1.0 op_sel_hi:[1,0]
	v_pk_add_f32 v[30:31], v[30:31], 1.0 op_sel_hi:[1,0]
	v_pk_fma_f32 v[28:29], v[32:33], v[28:29], v[36:37]
	v_pk_fma_f32 v[26:27], v[30:31], v[26:27], v[34:35]
	v_bfe_u32 v32, v28, 16, 1
	v_bfe_u32 v30, v26, 16, 1
	v_bfe_u32 v31, v27, 16, 1
	v_bfe_u32 v33, v29, 16, 1
	v_add3_u32 v26, v26, v30, s3
	v_add3_u32 v28, v28, v32, s3
	v_add3_u32 v27, v27, v31, s3
	v_add3_u32 v29, v29, v33, s3
	v_lshrrev_b32_e32 v26, 16, v26
	v_lshrrev_b32_e32 v28, 16, v28
	v_and_or_b32 v26, v27, s21, v26
	v_and_or_b32 v27, v29, s21, v28
	global_store_dwordx2 v[104:105], v[26:27], off offset:2560
	global_load_dwordx4 v[26:29], v[40:41], off
	s_nop 0
	global_load_dwordx4 v[30:33], v[38:39], off
	v_lshl_add_u64 v[36:37], s[18:19], 0, v[100:101]
	v_lshl_add_u64 v[34:35], s[16:17], 0, v[100:101]
	s_waitcnt vmcnt(0) lgkmcnt(0)
	v_pk_add_f32 v[28:29], v[28:29], 1.0 op_sel_hi:[1,0]
	v_pk_add_f32 v[26:27], v[26:27], 1.0 op_sel_hi:[1,0]
	v_pk_fma_f32 v[24:25], v[28:29], v[24:25], v[32:33]
	v_pk_fma_f32 v[22:23], v[26:27], v[22:23], v[30:31]
	v_bfe_u32 v28, v24, 16, 1
	v_bfe_u32 v26, v22, 16, 1
	v_bfe_u32 v27, v23, 16, 1
	v_bfe_u32 v29, v25, 16, 1
	v_add3_u32 v22, v22, v26, s3
	v_add3_u32 v24, v24, v28, s3
	v_add3_u32 v23, v23, v27, s3
	v_add3_u32 v25, v25, v29, s3
	v_lshrrev_b32_e32 v22, 16, v22
	v_lshrrev_b32_e32 v24, 16, v24
	v_and_or_b32 v22, v23, s21, v22
	v_and_or_b32 v23, v25, s21, v24
	global_store_dwordx2 v[104:105], v[22:23], off offset:3072
	global_load_dwordx4 v[22:25], v[36:37], off
	s_nop 0
	global_load_dwordx4 v[26:29], v[34:35], off
	s_waitcnt vmcnt(0) lgkmcnt(0)
	v_pk_add_f32 v[24:25], v[24:25], 1.0 op_sel_hi:[1,0]
	v_pk_add_f32 v[22:23], v[22:23], 1.0 op_sel_hi:[1,0]
	v_pk_fma_f32 v[20:21], v[20:21], v[24:25], v[28:29]
	v_pk_fma_f32 v[18:19], v[18:19], v[22:23], v[26:27]
	v_bfe_u32 v24, v20, 16, 1
	v_bfe_u32 v22, v18, 16, 1
	v_bfe_u32 v23, v19, 16, 1
	v_bfe_u32 v25, v21, 16, 1
	v_add3_u32 v18, v18, v22, s3
	v_add3_u32 v20, v20, v24, s3
	v_add3_u32 v19, v19, v23, s3
	v_add3_u32 v21, v21, v25, s3
	v_lshrrev_b32_e32 v18, 16, v18
	v_lshrrev_b32_e32 v20, 16, v20
	v_and_or_b32 v18, v19, s21, v18
	v_and_or_b32 v19, v21, s21, v20
	global_store_dwordx2 v[104:105], v[18:19], off offset:3584
	s_cbranch_scc1 .LBB0_3086

.LBB0_3149:
	v_mul_f32_e32 v130, 0xbfb8aa3b, v126
	v_exp_f32_e32 v130, v130
	v_mul_f32_e32 v138, 0xbfb8aa3b, v127
	v_exp_f32_e32 v138, v138
	s_lshl_b32 s5, s16, 7
	v_add_f32_e32 v133, 1.0, v130
	v_div_scale_f32 v134, s[8:9], v133, v133, v126
	v_rcp_f32_e32 v135, v134
	s_or_b32 s5, s36, s5
	v_or_b32_e32 v130, s5, v142
	v_add_u32_e32 v132, 0x4000, v1
	v_fma_f32 v136, -v134, v135, 1.0
	v_fmac_f32_e32 v135, v136, v135
	v_div_scale_f32 v136, vcc, v126, v133, v126
	v_mul_f32_e32 v137, v136, v135
	v_fma_f32 v139, -v134, v137, v136
	v_fmac_f32_e32 v137, v139, v135
	v_fma_f32 v134, -v134, v137, v136
	v_add_f32_e32 v136, 1.0, v138
	v_div_scale_f32 v138, s[8:9], v136, v136, v127
	v_rcp_f32_e32 v139, v138
	v_div_fmas_f32 v134, v134, v135, v137
	v_div_fixup_f32 v126, v134, v133, v126
	v_mul_f32_e32 v122, v126, v122
	v_fma_f32 v126, -v138, v139, 1.0
	v_fmac_f32_e32 v139, v126, v139
	v_div_scale_f32 v126, vcc, v127, v136, v127
	v_mul_f32_e32 v133, v126, v139
	v_fma_f32 v134, -v138, v133, v126
	v_fmac_f32_e32 v133, v134, v139
	v_mul_f32_e32 v134, 0xbfb8aa3b, v128
	v_exp_f32_e32 v134, v134
	v_fma_f32 v126, -v138, v133, v126
	v_div_fmas_f32 v126, v126, v139, v133
	v_div_fixup_f32 v126, v126, v136, v127
	v_add_f32_e32 v133, 1.0, v134
	v_div_scale_f32 v134, s[8:9], v133, v133, v128
	v_rcp_f32_e32 v135, v134
	v_mul_f32_e32 v123, v126, v123
	v_mul_f32_e32 v127, 0xbfb8aa3b, v129
	v_cvt_pk_bf16_f32 v122, v122, v123
	v_fma_f32 v123, -v134, v135, 1.0
	v_exp_f32_e32 v127, v127
	v_fmac_f32_e32 v135, v123, v135
	v_div_scale_f32 v123, vcc, v128, v133, v128
	v_mul_f32_e32 v126, v123, v135
	v_fma_f32 v136, -v134, v126, v123
	v_fmac_f32_e32 v126, v136, v135
	v_add_f32_e32 v127, 1.0, v127
	v_fma_f32 v123, -v134, v126, v123
	v_div_scale_f32 v134, s[8:9], v127, v127, v129
	v_rcp_f32_e32 v136, v134
	v_div_fmas_f32 v123, v123, v135, v126
	v_div_fixup_f32 v123, v123, v133, v128
	v_mul_f32_e32 v123, v123, v124
	v_fma_f32 v124, -v134, v136, 1.0
	v_fmac_f32_e32 v136, v124, v136
	v_div_scale_f32 v124, vcc, v129, v127, v129
	v_mul_f32_e32 v126, v124, v136
	v_fma_f32 v128, -v134, v126, v124
	v_fmac_f32_e32 v126, v128, v136
	v_mul_f32_e32 v128, 0xbfb8aa3b, v118
	v_exp_f32_e32 v128, v128
	v_fma_f32 v124, -v134, v126, v124
	v_div_fmas_f32 v124, v124, v136, v126
	v_div_fixup_f32 v124, v124, v127, v129
	v_add_f32_e32 v126, 1.0, v128
	v_div_scale_f32 v128, s[8:9], v126, v126, v118
	v_rcp_f32_e32 v133, v128
	v_mul_f32_e32 v124, v124, v125
	v_mul_f32_e32 v127, 0xbfb8aa3b, v119
	v_cvt_pk_bf16_f32 v123, v123, v124
	v_fma_f32 v124, -v128, v133, 1.0
	v_exp_f32_e32 v127, v127
	v_fmac_f32_e32 v133, v124, v133
	v_div_scale_f32 v124, vcc, v118, v126, v118
	v_mul_f32_e32 v125, v124, v133
	v_fma_f32 v129, -v128, v125, v124
	v_fmac_f32_e32 v125, v129, v133
	v_add_f32_e32 v127, 1.0, v127
	v_fma_f32 v124, -v128, v125, v124
	v_div_scale_f32 v128, s[8:9], v127, v127, v119
	v_rcp_f32_e32 v129, v128
	v_div_fmas_f32 v124, v124, v133, v125
	v_div_fixup_f32 v118, v124, v126, v118
	v_mul_f32_e32 v114, v118, v114
	v_fma_f32 v118, -v128, v129, 1.0
	v_fmac_f32_e32 v129, v118, v129
	v_div_scale_f32 v118, vcc, v119, v127, v119
	v_mul_f32_e32 v124, v118, v129
	v_fma_f32 v125, -v128, v124, v118
	v_fmac_f32_e32 v124, v125, v129
	v_mul_f32_e32 v125, 0xbfb8aa3b, v120
	v_exp_f32_e32 v125, v125
	v_fma_f32 v118, -v128, v124, v118
	v_div_fmas_f32 v118, v118, v129, v124
	v_div_fixup_f32 v118, v118, v127, v119
	v_add_f32_e32 v125, 1.0, v125
	v_div_scale_f32 v126, s[8:9], v125, v125, v120
	v_rcp_f32_e32 v128, v126
	v_mul_f32_e32 v115, v118, v115
	v_mul_f32_e32 v118, 0xbfb8aa3b, v121
	v_exp_f32_e32 v118, v118
	v_cvt_pk_bf16_f32 v124, v114, v115
	v_fma_f32 v114, -v126, v128, 1.0
	v_fmac_f32_e32 v128, v114, v128
	v_div_scale_f32 v114, vcc, v120, v125, v120
	v_mul_f32_e32 v115, v114, v128
	v_fma_f32 v119, -v126, v115, v114
	v_add_f32_e32 v118, 1.0, v118
	v_fmac_f32_e32 v115, v119, v128
	v_div_scale_f32 v119, s[8:9], v118, v118, v121
	v_fma_f32 v114, -v126, v115, v114
	v_rcp_f32_e32 v126, v119
	v_div_fmas_f32 v114, v114, v128, v115
	v_div_fixup_f32 v114, v114, v125, v120
	v_mul_f32_e32 v114, v114, v116
	v_fma_f32 v115, -v119, v126, 1.0
	v_fmac_f32_e32 v126, v115, v126
	v_div_scale_f32 v115, vcc, v121, v118, v121
	v_mul_f32_e32 v116, v115, v126
	v_fma_f32 v120, -v119, v116, v115
	v_fmac_f32_e32 v116, v120, v126
	v_fma_f32 v115, -v119, v116, v115
	v_div_fmas_f32 v115, v115, v126, v116
	v_div_fixup_f32 v115, v115, v118, v121
	v_mul_f32_e32 v115, v115, v117
	v_cvt_pk_bf16_f32 v125, v114, v115
	v_mul_f32_e32 v114, 0xbfb8aa3b, v110
	v_exp_f32_e32 v116, v114
	v_ashrrev_i32_e32 v131, 31, v130
	s_movk_i32 s5, 0x1600
	v_mov_b64_e32 v[114:115], s[22:23]
	v_add_f32_e32 v120, 1.0, v116
	v_div_scale_f32 v121, s[8:9], v120, v120, v110
	v_rcp_f32_e32 v126, v121
	v_mad_i64_i32 v[118:119], s[8:9], v132, s5, v[114:115]
	v_lshlrev_b64 v[116:117], 1, v[130:131]
	v_lshl_add_u64 v[118:119], v[118:119], 0, v[116:117]
	global_store_dwordx4 v[118:119], v[122:125], off
	v_fma_f32 v118, -v121, v126, 1.0
	v_fmac_f32_e32 v126, v118, v126
	v_mul_f32_e32 v122, 0xbfb8aa3b, v111
	v_div_scale_f32 v118, vcc, v110, v120, v110
	v_exp_f32_e32 v122, v122
	v_mul_f32_e32 v119, v118, v126
	v_fma_f32 v123, -v121, v119, v118
	v_fmac_f32_e32 v119, v123, v126
	v_fma_f32 v118, -v121, v119, v118
	v_add_f32_e32 v121, 1.0, v122
	v_div_scale_f32 v122, s[8:9], v121, v121, v111
	v_rcp_f32_e32 v123, v122
	v_div_fmas_f32 v118, v118, v126, v119
	v_div_fixup_f32 v110, v118, v120, v110
	v_mul_f32_e32 v106, v110, v106
	v_fma_f32 v110, -v122, v123, 1.0
	v_fmac_f32_e32 v123, v110, v123
	v_div_scale_f32 v110, vcc, v111, v121, v111
	v_mul_f32_e32 v118, v110, v123
	v_fma_f32 v119, -v122, v118, v110
	v_fmac_f32_e32 v118, v119, v123
	v_mul_f32_e32 v119, 0xbfb8aa3b, v112
	v_exp_f32_e32 v119, v119
	v_fma_f32 v110, -v122, v118, v110
	v_div_fmas_f32 v110, v110, v123, v118
	v_div_fixup_f32 v110, v110, v121, v111
	v_add_f32_e32 v118, 1.0, v119
	v_div_scale_f32 v119, s[8:9], v118, v118, v112
	v_rcp_f32_e32 v120, v119
	v_mul_f32_e32 v107, v110, v107
	v_mul_f32_e32 v111, 0xbfb8aa3b, v113
	v_cvt_pk_bf16_f32 v106, v106, v107
	v_fma_f32 v107, -v119, v120, 1.0
	v_exp_f32_e32 v111, v111
	v_fmac_f32_e32 v120, v107, v120
	v_div_scale_f32 v107, vcc, v112, v118, v112
	v_mul_f32_e32 v110, v107, v120
	v_fma_f32 v121, -v119, v110, v107
	v_fmac_f32_e32 v110, v121, v120
	v_add_f32_e32 v111, 1.0, v111
	v_fma_f32 v107, -v119, v110, v107
	v_div_scale_f32 v119, s[8:9], v111, v111, v113
	v_rcp_f32_e32 v121, v119
	v_div_fmas_f32 v107, v107, v120, v110
	v_div_fixup_f32 v107, v107, v118, v112
	v_mul_f32_e32 v107, v107, v108
	v_fma_f32 v108, -v119, v121, 1.0
	v_fmac_f32_e32 v121, v108, v121
	v_div_scale_f32 v108, vcc, v113, v111, v113
	v_mul_f32_e32 v110, v108, v121
	v_fma_f32 v112, -v119, v110, v108
	v_fmac_f32_e32 v110, v112, v121
	v_mul_f32_e32 v112, 0xbfb8aa3b, v102
	v_exp_f32_e32 v112, v112
	v_fma_f32 v108, -v119, v110, v108
	v_div_fmas_f32 v108, v108, v121, v110
	v_div_fixup_f32 v108, v108, v111, v113
	v_add_f32_e32 v110, 1.0, v112
	v_div_scale_f32 v112, s[8:9], v110, v110, v102
	v_rcp_f32_e32 v118, v112
	v_mul_f32_e32 v108, v108, v109
	v_mul_f32_e32 v111, 0xbfb8aa3b, v103
	v_cvt_pk_bf16_f32 v107, v107, v108
	v_fma_f32 v108, -v112, v118, 1.0
	v_exp_f32_e32 v111, v111
	v_fmac_f32_e32 v118, v108, v118
	v_div_scale_f32 v108, vcc, v102, v110, v102
	v_mul_f32_e32 v109, v108, v118
	v_fma_f32 v113, -v112, v109, v108
	v_fmac_f32_e32 v109, v113, v118
	v_add_f32_e32 v111, 1.0, v111
	v_fma_f32 v108, -v112, v109, v108
	v_div_scale_f32 v112, s[8:9], v111, v111, v103
	v_rcp_f32_e32 v113, v112
	v_div_fmas_f32 v108, v108, v118, v109
	v_div_fixup_f32 v102, v108, v110, v102
	v_mul_f32_e32 v98, v102, v98
	v_fma_f32 v102, -v112, v113, 1.0
	v_fmac_f32_e32 v113, v102, v113
	v_div_scale_f32 v102, vcc, v103, v111, v103
	v_mul_f32_e32 v108, v102, v113
	v_fma_f32 v109, -v112, v108, v102
	v_fmac_f32_e32 v108, v109, v113
	v_mul_f32_e32 v109, 0xbfb8aa3b, v104
	v_exp_f32_e32 v109, v109
	v_fma_f32 v102, -v112, v108, v102
	v_div_fmas_f32 v102, v102, v113, v108
	v_div_fixup_f32 v102, v102, v111, v103
	v_add_f32_e32 v109, 1.0, v109
	v_div_scale_f32 v110, s[8:9], v109, v109, v104
	v_rcp_f32_e32 v112, v110
	v_mul_f32_e32 v99, v102, v99
	v_mul_f32_e32 v102, 0xbfb8aa3b, v105
	v_exp_f32_e32 v102, v102
	v_cvt_pk_bf16_f32 v108, v98, v99
	v_fma_f32 v98, -v110, v112, 1.0
	v_fmac_f32_e32 v112, v98, v112
	v_div_scale_f32 v98, vcc, v104, v109, v104
	v_mul_f32_e32 v99, v98, v112
	v_fma_f32 v103, -v110, v99, v98
	v_add_f32_e32 v102, 1.0, v102
	v_fmac_f32_e32 v99, v103, v112
	v_div_scale_f32 v103, s[8:9], v102, v102, v105
	v_fma_f32 v98, -v110, v99, v98
	v_rcp_f32_e32 v110, v103
	v_div_fmas_f32 v98, v98, v112, v99
	v_div_fixup_f32 v98, v98, v109, v104
	v_mul_f32_e32 v98, v98, v100
	v_fma_f32 v99, -v103, v110, 1.0
	v_fmac_f32_e32 v110, v99, v110
	v_div_scale_f32 v99, vcc, v105, v102, v105
	v_mul_f32_e32 v100, v99, v110
	v_fma_f32 v104, -v103, v100, v99
	v_fmac_f32_e32 v100, v104, v110
	v_fma_f32 v99, -v103, v100, v99
	v_div_fmas_f32 v99, v99, v110, v100
	v_mul_f32_e32 v100, 0xbfb8aa3b, v94
	v_exp_f32_e32 v100, v100
	v_div_fixup_f32 v99, v99, v102, v105
	v_mul_f32_e32 v99, v99, v101
	v_cvt_pk_bf16_f32 v109, v98, v99
	v_add_f32_e32 v100, 1.0, v100
	v_div_scale_f32 v101, s[8:9], v100, v100, v94
	v_rcp_f32_e32 v102, v101
	v_add_u32_e32 v98, 0x4010, v1
	v_mad_i64_i32 v[98:99], s[8:9], v98, s5, v[114:115]
	v_lshl_add_u64 v[98:99], v[98:99], 0, v[116:117]
	global_store_dwordx4 v[98:99], v[106:109], off
	v_fma_f32 v98, -v101, v102, 1.0
	v_mul_f32_e32 v103, 0xbfb8aa3b, v95
	v_fmac_f32_e32 v102, v98, v102
	v_div_scale_f32 v98, vcc, v94, v100, v94
	v_exp_f32_e32 v103, v103
	v_mul_f32_e32 v99, v98, v102
	v_fma_f32 v104, -v101, v99, v98
	v_fmac_f32_e32 v99, v104, v102
	v_fma_f32 v98, -v101, v99, v98
	v_add_f32_e32 v101, 1.0, v103
	v_div_scale_f32 v103, s[8:9], v101, v101, v95
	v_rcp_f32_e32 v104, v103
	v_div_fmas_f32 v98, v98, v102, v99
	v_div_fixup_f32 v94, v98, v100, v94
	v_mul_f32_e32 v90, v94, v90
	v_fma_f32 v94, -v103, v104, 1.0
	v_fmac_f32_e32 v104, v94, v104
	v_div_scale_f32 v94, vcc, v95, v101, v95
	v_mul_f32_e32 v98, v94, v104
	v_fma_f32 v99, -v103, v98, v94
	v_fmac_f32_e32 v98, v99, v104
	v_mul_f32_e32 v99, 0xbfb8aa3b, v96
	v_exp_f32_e32 v99, v99
	v_fma_f32 v94, -v103, v98, v94
	v_div_fmas_f32 v94, v94, v104, v98
	v_div_fixup_f32 v94, v94, v101, v95
	v_add_f32_e32 v98, 1.0, v99
	v_div_scale_f32 v99, s[8:9], v98, v98, v96
	v_rcp_f32_e32 v100, v99
	v_mul_f32_e32 v91, v94, v91
	v_mul_f32_e32 v95, 0xbfb8aa3b, v97
	v_cvt_pk_bf16_f32 v90, v90, v91
	v_fma_f32 v91, -v99, v100, 1.0
	v_exp_f32_e32 v95, v95
	v_fmac_f32_e32 v100, v91, v100
	v_div_scale_f32 v91, vcc, v96, v98, v96
	v_mul_f32_e32 v94, v91, v100
	v_fma_f32 v101, -v99, v94, v91
	v_fmac_f32_e32 v94, v101, v100
	v_add_f32_e32 v95, 1.0, v95
	v_fma_f32 v91, -v99, v94, v91
	v_div_scale_f32 v99, s[8:9], v95, v95, v97
	v_rcp_f32_e32 v101, v99
	v_div_fmas_f32 v91, v91, v100, v94
	v_div_fixup_f32 v91, v91, v98, v96
	v_mul_f32_e32 v91, v91, v92
	v_fma_f32 v92, -v99, v101, 1.0
	v_fmac_f32_e32 v101, v92, v101
	v_div_scale_f32 v92, vcc, v97, v95, v97
	v_mul_f32_e32 v94, v92, v101
	v_fma_f32 v96, -v99, v94, v92
	v_fmac_f32_e32 v94, v96, v101
	v_mul_f32_e32 v96, 0xbfb8aa3b, v86
	v_exp_f32_e32 v96, v96
	v_fma_f32 v92, -v99, v94, v92
	v_div_fmas_f32 v92, v92, v101, v94
	v_div_fixup_f32 v92, v92, v95, v97
	v_add_f32_e32 v94, 1.0, v96
	v_div_scale_f32 v96, s[8:9], v94, v94, v86
	v_rcp_f32_e32 v98, v96
	v_mul_f32_e32 v92, v92, v93
	v_mul_f32_e32 v95, 0xbfb8aa3b, v87
	v_cvt_pk_bf16_f32 v91, v91, v92
	v_fma_f32 v92, -v96, v98, 1.0
	v_exp_f32_e32 v95, v95
	v_fmac_f32_e32 v98, v92, v98
	v_div_scale_f32 v92, vcc, v86, v94, v86
	v_mul_f32_e32 v93, v92, v98
	v_fma_f32 v97, -v96, v93, v92
	v_fmac_f32_e32 v93, v97, v98
	v_add_f32_e32 v95, 1.0, v95
	v_fma_f32 v92, -v96, v93, v92
	v_div_scale_f32 v96, s[8:9], v95, v95, v87
	v_rcp_f32_e32 v97, v96
	v_div_fmas_f32 v92, v92, v98, v93
	v_div_fixup_f32 v86, v92, v94, v86
	v_mul_f32_e32 v82, v86, v82
	v_fma_f32 v86, -v96, v97, 1.0
	v_fmac_f32_e32 v97, v86, v97
	v_div_scale_f32 v86, vcc, v87, v95, v87
	v_mul_f32_e32 v92, v86, v97
	v_fma_f32 v93, -v96, v92, v86
	v_fmac_f32_e32 v92, v93, v97
	v_mul_f32_e32 v93, 0xbfb8aa3b, v88
	v_exp_f32_e32 v93, v93
	v_fma_f32 v86, -v96, v92, v86
	v_div_fmas_f32 v86, v86, v97, v92
	v_div_fixup_f32 v86, v86, v95, v87
	v_add_f32_e32 v93, 1.0, v93
	v_div_scale_f32 v94, s[8:9], v93, v93, v88
	v_rcp_f32_e32 v96, v94
	v_mul_f32_e32 v83, v86, v83
	v_mul_f32_e32 v86, 0xbfb8aa3b, v89
	v_exp_f32_e32 v86, v86
	v_cvt_pk_bf16_f32 v92, v82, v83
	v_fma_f32 v82, -v94, v96, 1.0
	v_fmac_f32_e32 v96, v82, v96
	v_div_scale_f32 v82, vcc, v88, v93, v88
	v_mul_f32_e32 v83, v82, v96
	v_fma_f32 v87, -v94, v83, v82
	v_add_f32_e32 v86, 1.0, v86
	v_fmac_f32_e32 v83, v87, v96
	v_div_scale_f32 v87, s[8:9], v86, v86, v89
	v_fma_f32 v82, -v94, v83, v82
	v_rcp_f32_e32 v94, v87
	v_div_fmas_f32 v82, v82, v96, v83
	v_div_fixup_f32 v82, v82, v93, v88
	v_mul_f32_e32 v82, v82, v84
	v_fma_f32 v83, -v87, v94, 1.0
	v_fmac_f32_e32 v94, v83, v94
	v_div_scale_f32 v83, vcc, v89, v86, v89
	v_mul_f32_e32 v84, v83, v94
	v_fma_f32 v88, -v87, v84, v83
	v_fmac_f32_e32 v84, v88, v94
	v_fma_f32 v83, -v87, v84, v83
	v_div_fmas_f32 v83, v83, v94, v84
	v_mul_f32_e32 v84, 0xbfb8aa3b, v78
	v_exp_f32_e32 v84, v84
	v_div_fixup_f32 v83, v83, v86, v89
	v_mul_f32_e32 v83, v83, v85
	v_cvt_pk_bf16_f32 v93, v82, v83
	v_add_f32_e32 v84, 1.0, v84
	v_div_scale_f32 v85, s[8:9], v84, v84, v78
	v_rcp_f32_e32 v86, v85
	v_add_u32_e32 v82, 0x4020, v1
	v_mad_i64_i32 v[82:83], s[8:9], v82, s5, v[114:115]
	v_lshl_add_u64 v[82:83], v[82:83], 0, v[116:117]
	global_store_dwordx4 v[82:83], v[90:93], off
	v_fma_f32 v82, -v85, v86, 1.0
	v_mul_f32_e32 v87, 0xbfb8aa3b, v79
	v_fmac_f32_e32 v86, v82, v86
	v_div_scale_f32 v82, vcc, v78, v84, v78
	v_exp_f32_e32 v87, v87
	v_mul_f32_e32 v83, v82, v86
	v_fma_f32 v88, -v85, v83, v82
	v_fmac_f32_e32 v83, v88, v86
	v_fma_f32 v82, -v85, v83, v82
	v_add_f32_e32 v85, 1.0, v87
	v_div_scale_f32 v87, s[8:9], v85, v85, v79
	v_rcp_f32_e32 v88, v87
	v_div_fmas_f32 v82, v82, v86, v83
	v_div_fixup_f32 v78, v82, v84, v78
	v_mul_f32_e32 v74, v78, v74
	v_fma_f32 v78, -v87, v88, 1.0
	v_fmac_f32_e32 v88, v78, v88
	v_div_scale_f32 v78, vcc, v79, v85, v79
	v_mul_f32_e32 v82, v78, v88
	v_fma_f32 v83, -v87, v82, v78
	v_fmac_f32_e32 v82, v83, v88
	v_mul_f32_e32 v83, 0xbfb8aa3b, v80
	v_exp_f32_e32 v83, v83
	v_fma_f32 v78, -v87, v82, v78
	v_div_fmas_f32 v78, v78, v88, v82
	v_div_fixup_f32 v78, v78, v85, v79
	v_add_f32_e32 v82, 1.0, v83
	v_div_scale_f32 v83, s[8:9], v82, v82, v80
	v_rcp_f32_e32 v84, v83
	v_mul_f32_e32 v75, v78, v75
	v_mul_f32_e32 v79, 0xbfb8aa3b, v81
	v_cvt_pk_bf16_f32 v74, v74, v75
	v_fma_f32 v75, -v83, v84, 1.0
	v_exp_f32_e32 v79, v79
	v_fmac_f32_e32 v84, v75, v84
	v_div_scale_f32 v75, vcc, v80, v82, v80
	v_mul_f32_e32 v78, v75, v84
	v_fma_f32 v85, -v83, v78, v75
	v_fmac_f32_e32 v78, v85, v84
	v_add_f32_e32 v79, 1.0, v79
	v_fma_f32 v75, -v83, v78, v75
	v_div_scale_f32 v83, s[8:9], v79, v79, v81
	v_rcp_f32_e32 v85, v83
	v_div_fmas_f32 v75, v75, v84, v78
	v_div_fixup_f32 v75, v75, v82, v80
	v_mul_f32_e32 v75, v75, v76
	v_fma_f32 v76, -v83, v85, 1.0
	v_fmac_f32_e32 v85, v76, v85
	v_div_scale_f32 v76, vcc, v81, v79, v81
	v_mul_f32_e32 v78, v76, v85
	v_fma_f32 v80, -v83, v78, v76
	v_fmac_f32_e32 v78, v80, v85
	v_mul_f32_e32 v80, 0xbfb8aa3b, v70
	v_exp_f32_e32 v80, v80
	v_fma_f32 v76, -v83, v78, v76
	v_div_fmas_f32 v76, v76, v85, v78
	v_div_fixup_f32 v76, v76, v79, v81
	v_add_f32_e32 v78, 1.0, v80
	v_div_scale_f32 v80, s[8:9], v78, v78, v70
	v_rcp_f32_e32 v82, v80
	v_mul_f32_e32 v76, v76, v77
	v_mul_f32_e32 v79, 0xbfb8aa3b, v71
	v_cvt_pk_bf16_f32 v75, v75, v76
	v_fma_f32 v76, -v80, v82, 1.0
	v_exp_f32_e32 v79, v79
	v_fmac_f32_e32 v82, v76, v82
	v_div_scale_f32 v76, vcc, v70, v78, v70
	v_mul_f32_e32 v77, v76, v82
	v_fma_f32 v81, -v80, v77, v76
	v_fmac_f32_e32 v77, v81, v82
	v_add_f32_e32 v79, 1.0, v79
	v_fma_f32 v76, -v80, v77, v76
	v_div_scale_f32 v80, s[8:9], v79, v79, v71
	v_rcp_f32_e32 v81, v80
	v_div_fmas_f32 v76, v76, v82, v77
	v_div_fixup_f32 v70, v76, v78, v70
	v_mul_f32_e32 v66, v70, v66
	v_fma_f32 v70, -v80, v81, 1.0
	v_fmac_f32_e32 v81, v70, v81
	v_div_scale_f32 v70, vcc, v71, v79, v71
	v_mul_f32_e32 v76, v70, v81
	v_fma_f32 v77, -v80, v76, v70
	v_fmac_f32_e32 v76, v77, v81
	v_mul_f32_e32 v77, 0xbfb8aa3b, v72
	v_exp_f32_e32 v77, v77
	v_fma_f32 v70, -v80, v76, v70
	v_div_fmas_f32 v70, v70, v81, v76
	v_div_fixup_f32 v70, v70, v79, v71
	v_add_f32_e32 v77, 1.0, v77
	v_div_scale_f32 v78, s[8:9], v77, v77, v72
	v_rcp_f32_e32 v80, v78
	v_mul_f32_e32 v67, v70, v67
	v_mul_f32_e32 v70, 0xbfb8aa3b, v73
	v_exp_f32_e32 v70, v70
	v_cvt_pk_bf16_f32 v76, v66, v67
	v_fma_f32 v66, -v78, v80, 1.0
	v_fmac_f32_e32 v80, v66, v80
	v_div_scale_f32 v66, vcc, v72, v77, v72
	v_mul_f32_e32 v67, v66, v80
	v_fma_f32 v71, -v78, v67, v66
	v_add_f32_e32 v70, 1.0, v70
	v_fmac_f32_e32 v67, v71, v80
	v_div_scale_f32 v71, s[8:9], v70, v70, v73
	v_fma_f32 v66, -v78, v67, v66
	v_rcp_f32_e32 v78, v71
	v_div_fmas_f32 v66, v66, v80, v67
	v_div_fixup_f32 v66, v66, v77, v72
	v_mul_f32_e32 v66, v66, v68
	v_fma_f32 v67, -v71, v78, 1.0
	v_fmac_f32_e32 v78, v67, v78
	v_div_scale_f32 v67, vcc, v73, v70, v73
	v_mul_f32_e32 v68, v67, v78
	v_fma_f32 v72, -v71, v68, v67
	v_fmac_f32_e32 v68, v72, v78
	v_fma_f32 v67, -v71, v68, v67
	v_div_fmas_f32 v67, v67, v78, v68
	v_div_fixup_f32 v67, v67, v70, v73
	v_mul_f32_e32 v67, v67, v69
	v_cvt_pk_bf16_f32 v77, v66, v67
	v_mul_f32_e32 v66, 0xbfb8aa3b, v62
	v_exp_f32_e32 v68, v66
	v_add_u32_e32 v66, 0x4030, v1
	v_mad_i64_i32 v[66:67], s[8:9], v66, s5, v[114:115]
	v_add_f32_e32 v68, 1.0, v68
	v_div_scale_f32 v69, s[8:9], v68, v68, v62
	v_rcp_f32_e32 v70, v69
	v_lshl_add_u64 v[66:67], v[66:67], 0, v[116:117]
	global_store_dwordx4 v[66:67], v[74:77], off
	v_mul_f32_e32 v72, 0xbfb8aa3b, v63
	v_fma_f32 v67, -v69, v70, 1.0
	v_fmac_f32_e32 v70, v67, v70
	v_div_scale_f32 v67, vcc, v62, v68, v62
	v_exp_f32_e32 v72, v72
	v_mul_f32_e32 v71, v67, v70
	v_fma_f32 v73, -v69, v71, v67
	v_fmac_f32_e32 v71, v73, v70
	v_fma_f32 v67, -v69, v71, v67
	v_add_f32_e32 v69, 1.0, v72
	v_div_scale_f32 v72, s[8:9], v69, v69, v63
	v_rcp_f32_e32 v73, v72
	v_div_fmas_f32 v67, v67, v70, v71
	v_div_fixup_f32 v62, v67, v68, v62
	v_mul_f32_e32 v58, v62, v58
	v_fma_f32 v62, -v72, v73, 1.0
	v_fmac_f32_e32 v73, v62, v73
	v_div_scale_f32 v62, vcc, v63, v69, v63
	v_mul_f32_e32 v67, v62, v73
	v_fma_f32 v68, -v72, v67, v62
	v_fmac_f32_e32 v67, v68, v73
	v_mul_f32_e32 v68, 0xbfb8aa3b, v64
	v_exp_f32_e32 v68, v68
	v_fma_f32 v62, -v72, v67, v62
	v_div_fmas_f32 v62, v62, v73, v67
	v_div_fixup_f32 v62, v62, v69, v63
	v_add_f32_e32 v67, 1.0, v68
	v_div_scale_f32 v68, s[8:9], v67, v67, v64
	v_rcp_f32_e32 v70, v68
	v_mul_f32_e32 v59, v62, v59
	v_mul_f32_e32 v63, 0xbfb8aa3b, v65
	v_cvt_pk_bf16_f32 v58, v58, v59
	v_fma_f32 v59, -v68, v70, 1.0
	v_exp_f32_e32 v63, v63
	v_fmac_f32_e32 v70, v59, v70
	v_div_scale_f32 v59, vcc, v64, v67, v64
	v_mul_f32_e32 v62, v59, v70
	v_fma_f32 v69, -v68, v62, v59
	v_fmac_f32_e32 v62, v69, v70
	v_add_f32_e32 v63, 1.0, v63
	v_fma_f32 v59, -v68, v62, v59
	v_div_scale_f32 v68, s[8:9], v63, v63, v65
	v_rcp_f32_e32 v69, v68
	v_div_fmas_f32 v59, v59, v70, v62
	v_div_fixup_f32 v59, v59, v67, v64
	v_mul_f32_e32 v59, v59, v60
	v_fma_f32 v60, -v68, v69, 1.0
	v_fmac_f32_e32 v69, v60, v69
	v_div_scale_f32 v60, vcc, v65, v63, v65
	v_mul_f32_e32 v62, v60, v69
	v_fma_f32 v64, -v68, v62, v60
	v_fmac_f32_e32 v62, v64, v69
	v_mul_f32_e32 v64, 0xbfb8aa3b, v54
	v_exp_f32_e32 v64, v64
	v_fma_f32 v60, -v68, v62, v60
	v_div_fmas_f32 v60, v60, v69, v62
	v_div_fixup_f32 v60, v60, v63, v65
	v_add_f32_e32 v62, 1.0, v64
	v_div_scale_f32 v64, s[8:9], v62, v62, v54
	v_rcp_f32_e32 v67, v64
	v_mul_f32_e32 v60, v60, v61
	v_mul_f32_e32 v63, 0xbfb8aa3b, v55
	v_cvt_pk_bf16_f32 v59, v59, v60
	v_fma_f32 v60, -v64, v67, 1.0
	v_exp_f32_e32 v63, v63
	v_fmac_f32_e32 v67, v60, v67
	v_div_scale_f32 v60, vcc, v54, v62, v54
	v_mul_f32_e32 v61, v60, v67
	v_fma_f32 v65, -v64, v61, v60
	v_fmac_f32_e32 v61, v65, v67
	v_add_f32_e32 v63, 1.0, v63
	v_fma_f32 v60, -v64, v61, v60
	v_div_scale_f32 v64, s[8:9], v63, v63, v55
	v_rcp_f32_e32 v65, v64
	v_div_fmas_f32 v60, v60, v67, v61
	v_div_fixup_f32 v54, v60, v62, v54
	v_mul_f32_e32 v50, v54, v50
	v_fma_f32 v54, -v64, v65, 1.0
	v_fmac_f32_e32 v65, v54, v65
	v_div_scale_f32 v54, vcc, v55, v63, v55
	v_mul_f32_e32 v60, v54, v65
	v_fma_f32 v61, -v64, v60, v54
	v_fmac_f32_e32 v60, v61, v65
	v_mul_f32_e32 v61, 0xbfb8aa3b, v56
	v_exp_f32_e32 v61, v61
	v_fma_f32 v54, -v64, v60, v54
	v_div_fmas_f32 v54, v54, v65, v60
	v_div_fixup_f32 v54, v54, v63, v55
	v_add_f32_e32 v61, 1.0, v61
	v_div_scale_f32 v62, s[8:9], v61, v61, v56
	v_rcp_f32_e32 v64, v62
	v_mul_f32_e32 v51, v54, v51
	v_mul_f32_e32 v54, 0xbfb8aa3b, v57
	v_exp_f32_e32 v54, v54
	v_cvt_pk_bf16_f32 v60, v50, v51
	v_fma_f32 v50, -v62, v64, 1.0
	v_fmac_f32_e32 v64, v50, v64
	v_div_scale_f32 v50, vcc, v56, v61, v56
	v_mul_f32_e32 v51, v50, v64
	v_fma_f32 v55, -v62, v51, v50
	v_add_f32_e32 v54, 1.0, v54
	v_fmac_f32_e32 v51, v55, v64
	v_div_scale_f32 v55, s[8:9], v54, v54, v57
	v_fma_f32 v50, -v62, v51, v50
	v_rcp_f32_e32 v62, v55
	v_div_fmas_f32 v50, v50, v64, v51
	v_div_fixup_f32 v50, v50, v61, v56
	v_mul_f32_e32 v50, v50, v52
	v_fma_f32 v51, -v55, v62, 1.0
	v_fmac_f32_e32 v62, v51, v62
	v_div_scale_f32 v51, vcc, v57, v54, v57
	v_mul_f32_e32 v52, v51, v62
	v_fma_f32 v56, -v55, v52, v51
	v_fmac_f32_e32 v52, v56, v62
	v_fma_f32 v51, -v55, v52, v51
	v_div_fmas_f32 v51, v51, v62, v52
	v_mul_f32_e32 v52, 0xbfb8aa3b, v46
	v_exp_f32_e32 v52, v52
	v_div_fixup_f32 v51, v51, v54, v57
	v_mul_f32_e32 v51, v51, v53
	v_add_u32_e32 v66, 0x4080, v1
	v_add_f32_e32 v52, 1.0, v52
	v_div_scale_f32 v53, s[8:9], v52, v52, v46
	v_rcp_f32_e32 v54, v53
	v_cvt_pk_bf16_f32 v61, v50, v51
	v_mad_i64_i32 v[50:51], s[8:9], v66, s5, v[114:115]
	v_lshl_add_u64 v[50:51], v[50:51], 0, v[116:117]
	global_store_dwordx4 v[50:51], v[58:61], off
	v_fma_f32 v50, -v53, v54, 1.0
	v_mul_f32_e32 v55, 0xbfb8aa3b, v47
	v_fmac_f32_e32 v54, v50, v54
	v_div_scale_f32 v50, vcc, v46, v52, v46
	v_exp_f32_e32 v55, v55
	v_mul_f32_e32 v51, v50, v54
	v_fma_f32 v56, -v53, v51, v50
	v_fmac_f32_e32 v51, v56, v54
	v_fma_f32 v50, -v53, v51, v50
	v_add_f32_e32 v53, 1.0, v55
	v_div_scale_f32 v55, s[8:9], v53, v53, v47
	v_rcp_f32_e32 v56, v55
	v_div_fmas_f32 v50, v50, v54, v51
	v_div_fixup_f32 v46, v50, v52, v46
	v_mul_f32_e32 v42, v46, v42
	v_fma_f32 v46, -v55, v56, 1.0
	v_fmac_f32_e32 v56, v46, v56
	v_div_scale_f32 v46, vcc, v47, v53, v47
	v_mul_f32_e32 v50, v46, v56
	v_fma_f32 v51, -v55, v50, v46
	v_fmac_f32_e32 v50, v51, v56
	v_mul_f32_e32 v51, 0xbfb8aa3b, v48
	v_exp_f32_e32 v51, v51
	v_fma_f32 v46, -v55, v50, v46
	v_div_fmas_f32 v46, v46, v56, v50
	v_div_fixup_f32 v46, v46, v53, v47
	v_add_f32_e32 v50, 1.0, v51
	v_div_scale_f32 v51, s[8:9], v50, v50, v48
	v_rcp_f32_e32 v52, v51
	v_mul_f32_e32 v43, v46, v43
	v_mul_f32_e32 v47, 0xbfb8aa3b, v49
	v_cvt_pk_bf16_f32 v42, v42, v43
	v_fma_f32 v43, -v51, v52, 1.0
	v_exp_f32_e32 v47, v47
	v_fmac_f32_e32 v52, v43, v52
	v_div_scale_f32 v43, vcc, v48, v50, v48
	v_mul_f32_e32 v46, v43, v52
	v_fma_f32 v53, -v51, v46, v43
	v_fmac_f32_e32 v46, v53, v52
	v_add_f32_e32 v47, 1.0, v47
	v_fma_f32 v43, -v51, v46, v43
	v_div_scale_f32 v51, s[8:9], v47, v47, v49
	v_rcp_f32_e32 v53, v51
	v_div_fmas_f32 v43, v43, v52, v46
	v_div_fixup_f32 v43, v43, v50, v48
	v_mul_f32_e32 v43, v43, v44
	v_fma_f32 v44, -v51, v53, 1.0
	v_fmac_f32_e32 v53, v44, v53
	v_div_scale_f32 v44, vcc, v49, v47, v49
	v_mul_f32_e32 v46, v44, v53
	v_fma_f32 v48, -v51, v46, v44
	v_fmac_f32_e32 v46, v48, v53
	v_mul_f32_e32 v48, 0xbfb8aa3b, v38
	v_exp_f32_e32 v48, v48
	v_fma_f32 v44, -v51, v46, v44
	v_div_fmas_f32 v44, v44, v53, v46
	v_div_fixup_f32 v44, v44, v47, v49
	v_add_f32_e32 v46, 1.0, v48
	v_div_scale_f32 v48, s[8:9], v46, v46, v38
	v_rcp_f32_e32 v50, v48
	v_mul_f32_e32 v44, v44, v45
	v_mul_f32_e32 v47, 0xbfb8aa3b, v39
	v_cvt_pk_bf16_f32 v43, v43, v44
	v_fma_f32 v44, -v48, v50, 1.0
	v_exp_f32_e32 v47, v47
	v_fmac_f32_e32 v50, v44, v50
	v_div_scale_f32 v44, vcc, v38, v46, v38
	v_mul_f32_e32 v45, v44, v50
	v_fma_f32 v49, -v48, v45, v44
	v_fmac_f32_e32 v45, v49, v50
	v_add_f32_e32 v47, 1.0, v47
	v_fma_f32 v44, -v48, v45, v44
	v_div_scale_f32 v48, s[8:9], v47, v47, v39
	v_rcp_f32_e32 v49, v48
	v_div_fmas_f32 v44, v44, v50, v45
	v_div_fixup_f32 v38, v44, v46, v38
	v_mul_f32_e32 v34, v38, v34
	v_fma_f32 v38, -v48, v49, 1.0
	v_fmac_f32_e32 v49, v38, v49
	v_div_scale_f32 v38, vcc, v39, v47, v39
	v_mul_f32_e32 v44, v38, v49
	v_fma_f32 v45, -v48, v44, v38
	v_fmac_f32_e32 v44, v45, v49
	v_mul_f32_e32 v45, 0xbfb8aa3b, v40
	v_exp_f32_e32 v45, v45
	v_fma_f32 v38, -v48, v44, v38
	v_div_fmas_f32 v38, v38, v49, v44
	v_div_fixup_f32 v38, v38, v47, v39
	v_add_f32_e32 v45, 1.0, v45
	v_div_scale_f32 v46, s[8:9], v45, v45, v40
	v_rcp_f32_e32 v48, v46
	v_mul_f32_e32 v35, v38, v35
	v_mul_f32_e32 v38, 0xbfb8aa3b, v41
	v_exp_f32_e32 v38, v38
	v_cvt_pk_bf16_f32 v44, v34, v35
	v_fma_f32 v34, -v46, v48, 1.0
	v_fmac_f32_e32 v48, v34, v48
	v_div_scale_f32 v34, vcc, v40, v45, v40
	v_mul_f32_e32 v35, v34, v48
	v_fma_f32 v39, -v46, v35, v34
	v_add_f32_e32 v38, 1.0, v38
	v_fmac_f32_e32 v35, v39, v48
	v_div_scale_f32 v39, s[8:9], v38, v38, v41
	v_fma_f32 v34, -v46, v35, v34
	v_rcp_f32_e32 v46, v39
	v_div_fmas_f32 v34, v34, v48, v35
	v_div_fixup_f32 v34, v34, v45, v40
	v_mul_f32_e32 v34, v34, v36
	v_fma_f32 v35, -v39, v46, 1.0
	v_fmac_f32_e32 v46, v35, v46
	v_div_scale_f32 v35, vcc, v41, v38, v41
	v_mul_f32_e32 v36, v35, v46
	v_fma_f32 v40, -v39, v36, v35
	v_fmac_f32_e32 v36, v40, v46
	v_fma_f32 v35, -v39, v36, v35
	v_div_fmas_f32 v35, v35, v46, v36
	v_mul_f32_e32 v36, 0xbfb8aa3b, v30
	v_exp_f32_e32 v36, v36
	v_div_fixup_f32 v35, v35, v38, v41
	v_mul_f32_e32 v35, v35, v37
	v_cvt_pk_bf16_f32 v45, v34, v35
	v_add_f32_e32 v36, 1.0, v36
	v_div_scale_f32 v37, s[8:9], v36, v36, v30
	v_rcp_f32_e32 v38, v37
	v_add_u32_e32 v34, 0x4090, v1
	v_mad_i64_i32 v[34:35], s[8:9], v34, s5, v[114:115]
	v_lshl_add_u64 v[34:35], v[34:35], 0, v[116:117]
	global_store_dwordx4 v[34:35], v[42:45], off
	v_fma_f32 v34, -v37, v38, 1.0
	v_mul_f32_e32 v39, 0xbfb8aa3b, v31
	v_fmac_f32_e32 v38, v34, v38
	v_div_scale_f32 v34, vcc, v30, v36, v30
	v_exp_f32_e32 v39, v39
	v_mul_f32_e32 v35, v34, v38
	v_fma_f32 v40, -v37, v35, v34
	v_fmac_f32_e32 v35, v40, v38
	v_fma_f32 v34, -v37, v35, v34
	v_add_f32_e32 v37, 1.0, v39
	v_div_scale_f32 v39, s[8:9], v37, v37, v31
	v_rcp_f32_e32 v40, v39
	v_div_fmas_f32 v34, v34, v38, v35
	v_div_fixup_f32 v30, v34, v36, v30
	v_mul_f32_e32 v26, v30, v26
	v_fma_f32 v30, -v39, v40, 1.0
	v_fmac_f32_e32 v40, v30, v40
	v_div_scale_f32 v30, vcc, v31, v37, v31
	v_mul_f32_e32 v34, v30, v40
	v_fma_f32 v35, -v39, v34, v30
	v_fmac_f32_e32 v34, v35, v40
	v_mul_f32_e32 v35, 0xbfb8aa3b, v32
	v_exp_f32_e32 v35, v35
	v_fma_f32 v30, -v39, v34, v30
	v_div_fmas_f32 v30, v30, v40, v34
	v_div_fixup_f32 v30, v30, v37, v31
	v_add_f32_e32 v34, 1.0, v35
	v_div_scale_f32 v35, s[8:9], v34, v34, v32
	v_rcp_f32_e32 v36, v35
	v_mul_f32_e32 v27, v30, v27
	v_mul_f32_e32 v31, 0xbfb8aa3b, v33
	v_cvt_pk_bf16_f32 v26, v26, v27
	v_fma_f32 v27, -v35, v36, 1.0
	v_exp_f32_e32 v31, v31
	v_fmac_f32_e32 v36, v27, v36
	v_div_scale_f32 v27, vcc, v32, v34, v32
	v_mul_f32_e32 v30, v27, v36
	v_fma_f32 v37, -v35, v30, v27
	v_fmac_f32_e32 v30, v37, v36
	v_add_f32_e32 v31, 1.0, v31
	v_fma_f32 v27, -v35, v30, v27
	v_div_scale_f32 v35, s[8:9], v31, v31, v33
	v_rcp_f32_e32 v37, v35
	v_div_fmas_f32 v27, v27, v36, v30
	v_div_fixup_f32 v27, v27, v34, v32
	v_mul_f32_e32 v27, v27, v28
	v_fma_f32 v28, -v35, v37, 1.0
	v_fmac_f32_e32 v37, v28, v37
	v_div_scale_f32 v28, vcc, v33, v31, v33
	v_mul_f32_e32 v30, v28, v37
	v_fma_f32 v32, -v35, v30, v28
	v_fmac_f32_e32 v30, v32, v37
	v_mul_f32_e32 v32, 0xbfb8aa3b, v22
	v_exp_f32_e32 v32, v32
	v_fma_f32 v28, -v35, v30, v28
	v_div_fmas_f32 v28, v28, v37, v30
	v_div_fixup_f32 v28, v28, v31, v33
	v_add_f32_e32 v30, 1.0, v32
	v_div_scale_f32 v32, s[8:9], v30, v30, v22
	v_rcp_f32_e32 v34, v32
	v_mul_f32_e32 v28, v28, v29
	v_mul_f32_e32 v31, 0xbfb8aa3b, v23
	v_cvt_pk_bf16_f32 v27, v27, v28
	v_fma_f32 v28, -v32, v34, 1.0
	v_exp_f32_e32 v31, v31
	v_fmac_f32_e32 v34, v28, v34
	v_div_scale_f32 v28, vcc, v22, v30, v22
	v_mul_f32_e32 v29, v28, v34
	v_fma_f32 v33, -v32, v29, v28
	v_fmac_f32_e32 v29, v33, v34
	v_add_f32_e32 v31, 1.0, v31
	v_fma_f32 v28, -v32, v29, v28
	v_div_scale_f32 v32, s[8:9], v31, v31, v23
	v_rcp_f32_e32 v33, v32
	v_div_fmas_f32 v28, v28, v34, v29
	v_div_fixup_f32 v22, v28, v30, v22
	v_mul_f32_e32 v18, v22, v18
	v_fma_f32 v22, -v32, v33, 1.0
	v_fmac_f32_e32 v33, v22, v33
	v_div_scale_f32 v22, vcc, v23, v31, v23
	v_mul_f32_e32 v28, v22, v33
	v_fma_f32 v29, -v32, v28, v22
	v_fmac_f32_e32 v28, v29, v33
	v_mul_f32_e32 v29, 0xbfb8aa3b, v24
	v_exp_f32_e32 v29, v29
	v_fma_f32 v22, -v32, v28, v22
	v_div_fmas_f32 v22, v22, v33, v28
	v_div_fixup_f32 v22, v22, v31, v23
	v_add_f32_e32 v29, 1.0, v29
	v_div_scale_f32 v30, s[8:9], v29, v29, v24
	v_rcp_f32_e32 v32, v30
	v_mul_f32_e32 v19, v22, v19
	v_mul_f32_e32 v22, 0xbfb8aa3b, v25
	v_exp_f32_e32 v22, v22
	v_cvt_pk_bf16_f32 v28, v18, v19
	v_fma_f32 v18, -v30, v32, 1.0
	v_fmac_f32_e32 v32, v18, v32
	v_div_scale_f32 v18, vcc, v24, v29, v24
	v_mul_f32_e32 v19, v18, v32
	v_fma_f32 v23, -v30, v19, v18
	v_add_f32_e32 v22, 1.0, v22
	v_fmac_f32_e32 v19, v23, v32
	v_div_scale_f32 v23, s[8:9], v22, v22, v25
	v_fma_f32 v18, -v30, v19, v18
	v_rcp_f32_e32 v30, v23
	v_div_fmas_f32 v18, v18, v32, v19
	v_div_fixup_f32 v18, v18, v29, v24
	v_mul_f32_e32 v18, v18, v20
	v_fma_f32 v19, -v23, v30, 1.0
	v_fmac_f32_e32 v30, v19, v30
	v_div_scale_f32 v19, vcc, v25, v22, v25
	v_mul_f32_e32 v20, v19, v30
	v_fma_f32 v24, -v23, v20, v19
	v_fmac_f32_e32 v20, v24, v30
	v_fma_f32 v19, -v23, v20, v19
	v_div_fmas_f32 v19, v19, v30, v20
	v_mul_f32_e32 v20, 0xbfb8aa3b, v14
	v_exp_f32_e32 v20, v20
	v_div_fixup_f32 v19, v19, v22, v25
	v_mul_f32_e32 v19, v19, v21
	v_cvt_pk_bf16_f32 v29, v18, v19
	v_add_f32_e32 v20, 1.0, v20
	v_div_scale_f32 v21, s[8:9], v20, v20, v14
	v_rcp_f32_e32 v22, v21
	v_add_u32_e32 v18, 0x40a0, v1
	v_mad_i64_i32 v[18:19], s[8:9], v18, s5, v[114:115]
	v_lshl_add_u64 v[18:19], v[18:19], 0, v[116:117]
	global_store_dwordx4 v[18:19], v[26:29], off
	v_fma_f32 v18, -v21, v22, 1.0
	v_mul_f32_e32 v23, 0xbfb8aa3b, v15
	v_fmac_f32_e32 v22, v18, v22
	v_div_scale_f32 v18, vcc, v14, v20, v14
	v_exp_f32_e32 v23, v23
	v_mul_f32_e32 v19, v18, v22
	v_fma_f32 v24, -v21, v19, v18
	v_fmac_f32_e32 v19, v24, v22
	v_fma_f32 v18, -v21, v19, v18
	v_add_f32_e32 v21, 1.0, v23
	v_div_scale_f32 v23, s[8:9], v21, v21, v15
	v_rcp_f32_e32 v24, v23
	v_div_fmas_f32 v18, v18, v22, v19
	v_div_fixup_f32 v14, v18, v20, v14
	v_mul_f32_e32 v10, v14, v10
	v_fma_f32 v14, -v23, v24, 1.0
	v_fmac_f32_e32 v24, v14, v24
	v_div_scale_f32 v14, vcc, v15, v21, v15
	v_mul_f32_e32 v18, v14, v24
	v_fma_f32 v19, -v23, v18, v14
	v_fmac_f32_e32 v18, v19, v24
	v_mul_f32_e32 v19, 0xbfb8aa3b, v16
	v_exp_f32_e32 v19, v19
	v_fma_f32 v14, -v23, v18, v14
	v_div_fmas_f32 v14, v14, v24, v18
	v_div_fixup_f32 v14, v14, v21, v15
	v_add_f32_e32 v18, 1.0, v19
	v_div_scale_f32 v19, s[8:9], v18, v18, v16
	v_rcp_f32_e32 v20, v19
	v_mul_f32_e32 v11, v14, v11
	v_mul_f32_e32 v15, 0xbfb8aa3b, v17
	v_cvt_pk_bf16_f32 v10, v10, v11
	v_fma_f32 v11, -v19, v20, 1.0
	v_exp_f32_e32 v15, v15
	v_fmac_f32_e32 v20, v11, v20
	v_div_scale_f32 v11, vcc, v16, v18, v16
	v_mul_f32_e32 v14, v11, v20
	v_fma_f32 v21, -v19, v14, v11
	v_fmac_f32_e32 v14, v21, v20
	v_add_f32_e32 v15, 1.0, v15
	v_fma_f32 v11, -v19, v14, v11
	v_div_scale_f32 v19, s[8:9], v15, v15, v17
	v_rcp_f32_e32 v21, v19
	v_div_fmas_f32 v11, v11, v20, v14
	v_div_fixup_f32 v11, v11, v18, v16
	v_mul_f32_e32 v11, v11, v12
	v_fma_f32 v12, -v19, v21, 1.0
	v_fmac_f32_e32 v21, v12, v21
	v_div_scale_f32 v12, vcc, v17, v15, v17
	v_mul_f32_e32 v14, v12, v21
	v_fma_f32 v16, -v19, v14, v12
	v_fmac_f32_e32 v14, v16, v21
	v_mul_f32_e32 v16, 0xbfb8aa3b, v6
	v_exp_f32_e32 v16, v16
	v_fma_f32 v12, -v19, v14, v12
	v_div_fmas_f32 v12, v12, v21, v14
	v_div_fixup_f32 v12, v12, v15, v17
	v_add_f32_e32 v14, 1.0, v16
	v_div_scale_f32 v16, s[8:9], v14, v14, v6
	v_rcp_f32_e32 v18, v16
	v_mul_f32_e32 v12, v12, v13
	v_mul_f32_e32 v15, 0xbfb8aa3b, v7
	v_cvt_pk_bf16_f32 v11, v11, v12
	v_fma_f32 v12, -v16, v18, 1.0
	v_exp_f32_e32 v15, v15
	v_fmac_f32_e32 v18, v12, v18
	v_div_scale_f32 v12, vcc, v6, v14, v6
	v_mul_f32_e32 v13, v12, v18
	v_fma_f32 v17, -v16, v13, v12
	v_fmac_f32_e32 v13, v17, v18
	v_add_f32_e32 v15, 1.0, v15
	v_fma_f32 v12, -v16, v13, v12
	v_div_scale_f32 v16, s[8:9], v15, v15, v7
	v_rcp_f32_e32 v17, v16
	v_div_fmas_f32 v12, v12, v18, v13
	v_div_fixup_f32 v6, v12, v14, v6
	v_mul_f32_e32 v2, v6, v2
	v_fma_f32 v6, -v16, v17, 1.0
	v_fmac_f32_e32 v17, v6, v17
	v_div_scale_f32 v6, vcc, v7, v15, v7
	v_mul_f32_e32 v12, v6, v17
	v_fma_f32 v13, -v16, v12, v6
	v_fmac_f32_e32 v12, v13, v17
	v_mul_f32_e32 v13, 0xbfb8aa3b, v8
	v_exp_f32_e32 v13, v13
	v_fma_f32 v6, -v16, v12, v6
	v_div_fmas_f32 v6, v6, v17, v12
	v_div_fixup_f32 v6, v6, v15, v7
	v_add_f32_e32 v13, 1.0, v13
	v_div_scale_f32 v14, s[8:9], v13, v13, v8
	v_rcp_f32_e32 v16, v14
	v_mul_f32_e32 v3, v6, v3
	v_mul_f32_e32 v6, 0xbfb8aa3b, v9
	v_exp_f32_e32 v6, v6
	v_cvt_pk_bf16_f32 v12, v2, v3
	v_fma_f32 v2, -v14, v16, 1.0
	v_fmac_f32_e32 v16, v2, v16
	v_div_scale_f32 v2, vcc, v8, v13, v8
	v_mul_f32_e32 v3, v2, v16
	v_fma_f32 v7, -v14, v3, v2
	v_add_f32_e32 v6, 1.0, v6
	v_fmac_f32_e32 v3, v7, v16
	v_div_scale_f32 v7, s[8:9], v6, v6, v9
	v_fma_f32 v2, -v14, v3, v2
	v_rcp_f32_e32 v14, v7
	v_div_fmas_f32 v2, v2, v16, v3
	v_div_fixup_f32 v2, v2, v13, v8
	v_mul_f32_e32 v2, v2, v4
	v_fma_f32 v3, -v7, v14, 1.0
	v_fmac_f32_e32 v14, v3, v14
	v_div_scale_f32 v3, vcc, v9, v6, v9
	v_mul_f32_e32 v4, v3, v14
	v_fma_f32 v8, -v7, v4, v3
	v_fmac_f32_e32 v4, v8, v14
	v_fma_f32 v3, -v7, v4, v3
	v_div_fmas_f32 v3, v3, v14, v4
	v_div_fixup_f32 v3, v3, v6, v9
	v_mul_f32_e32 v3, v3, v5
	v_add_u32_e32 v1, 0x40b0, v1
	v_cvt_pk_bf16_f32 v13, v2, v3
	v_mad_i64_i32 v[2:3], s[8:9], v1, s5, v[114:115]
	v_lshl_add_u64 v[2:3], v[2:3], 0, v[116:117]
	global_store_dwordx4 v[2:3], v[10:13], off
	s_waitcnt vmcnt(0)
	s_barrier
	s_waitcnt vmcnt(0)
	s_waitcnt vmcnt(0) lgkmcnt(0)
	s_barrier
	s_mov_b64 s[8:9], exec
	v_readlane_b32 s10, v228, 2
	v_readlane_b32 s11, v228, 3
	s_and_b64 s[10:11], s[8:9], s[10:11]
	s_mov_b64 exec, s[10:11]
	s_cbranch_execz .LBB0_3152
	s_mov_b64 s[10:11], exec
	v_mbcnt_lo_u32_b32 v1, s10, 0
	buffer_wbl2 sc1
	s_waitcnt vmcnt(0)
	v_mbcnt_hi_u32_b32 v1, s11, v1
	v_cmp_eq_u32_e32 vcc, 0, v1
	s_and_b64 s[24:25], exec, vcc
	s_mov_b64 exec, s[24:25]
	s_cbranch_execz .LBB0_3152
	s_bcnt1_i32_b64 s5, s[10:11]
	v_mov_b32_e32 v1, 0
	v_mov_b32_e32 v2, s5
	global_atomic_add v1, v2, s[6:7]

.LBB0_3168:
	s_add_u32 s6, s12, 0x7800000
	s_addc_u32 s7, s13, 0
	s_lshl_b32 s9, s17, 8
	s_add_i32 s8, s5, 0x4000
	v_lshl_or_b32 v130, v138, 2, s9
	v_or_b32_e32 v130, s40, v130
	v_or_b32_e32 v134, s8, v1
	s_movk_i32 s11, 0x4080
	s_movk_i32 s24, 0x4000
	s_ashr_i32 s10, s8, 13
	v_cmp_gt_i32_e32 vcc, s11, v134
	v_or_b32_e32 v132, 16, v130
	s_and_saveexec_b64 s[8:9], vcc
	s_cbranch_execz .LBB0_3170
	v_add_u32_e32 v131, 0xffffc002, v134
	v_mov_b32_e32 v133, s10
	v_cmp_gt_i32_e32 vcc, s24, v134
	s_mov_b32 s17, 0x9000
	v_mov_b64_e32 v[136:137], s[14:15]
	v_cndmask_b32_e32 v131, v131, v133, vcc
	v_mad_i64_i32 v[136:137], s[24:25], v131, s17, v[136:137]
	s_mov_b64 s[24:25], 0x8000
	v_ashrrev_i32_e32 v135, 31, v134
	v_lshl_add_u64 v[148:149], v[136:137], 0, s[24:25]
	v_lshlrev_b64 v[136:137], 12, v[134:135]
	v_add_u32_e32 v150, 0xffffc000, v134
	v_mov_b32_e32 v151, 0
	v_lshl_add_u64 v[144:145], s[6:7], 0, v[136:137]
	v_lshlrev_b64 v[136:137], 12, v[150:151]
	v_mov_b32_e32 v131, v151
	v_lshl_add_u64 v[136:137], s[18:19], 0, v[136:137]
	v_lshlrev_b64 v[146:147], 2, v[130:131]
	v_cndmask_b32_e32 v141, v137, v145, vcc
	v_cndmask_b32_e32 v140, v136, v144, vcc
	v_lshl_add_u64 v[136:137], v[148:149], 0, v[146:147]
	global_load_dwordx4 v[136:139], v[136:137], off
	v_lshl_add_u64 v[152:153], v[140:141], 0, v[146:147]
	global_load_dwordx4 v[140:143], v[152:153], off
	v_mov_b32_e32 v133, v151
	v_lshl_add_u64 v[154:155], v[144:145], 0, v[146:147]
	v_lshl_add_u64 v[144:145], v[132:133], 2, v[148:149]
	global_load_dwordx4 v[144:147], v[144:145], off
	v_or_b32_e32 v150, 0x80, v130
	s_waitcnt vmcnt(0) lgkmcnt(0)
	v_pk_mul_f32 v[128:129], v[128:129], v[138:139]
	v_pk_mul_f32 v[126:127], v[126:127], v[136:137]
	v_pk_fma_f32 v[128:129], v[128:129], 0.5, v[142:143] op_sel_hi:[1,0,1]
	v_pk_fma_f32 v[126:127], v[126:127], 0.5, v[140:141] op_sel_hi:[1,0,1]
	global_store_dwordx4 v[154:155], v[126:129], off
	global_load_dwordx4 v[126:129], v[152:153], off offset:64
	v_pk_mul_f32 v[124:125], v[124:125], v[146:147]
	v_pk_mul_f32 v[122:123], v[122:123], v[144:145]
	v_lshl_add_u64 v[136:137], v[150:151], 2, v[148:149]
	global_load_dwordx4 v[136:139], v[136:137], off
	v_or_b32_e32 v150, 0x90, v130
	s_waitcnt vmcnt(0) lgkmcnt(0)
	v_pk_fma_f32 v[124:125], v[124:125], 0.5, v[128:129] op_sel_hi:[1,0,1]
	v_pk_fma_f32 v[122:123], v[122:123], 0.5, v[126:127] op_sel_hi:[1,0,1]
	global_store_dwordx4 v[154:155], v[122:125], off offset:64
	global_load_dwordx4 v[122:125], v[152:153], off offset:512
	v_lshl_add_u64 v[126:127], v[150:151], 2, v[148:149]
	global_load_dwordx4 v[126:129], v[126:127], off
	v_pk_mul_f32 v[120:121], v[120:121], v[138:139]
	v_pk_mul_f32 v[118:119], v[118:119], v[136:137]
	s_waitcnt vmcnt(0) lgkmcnt(0)
	v_pk_fma_f32 v[120:121], v[120:121], 0.5, v[124:125] op_sel_hi:[1,0,1]
	v_pk_fma_f32 v[118:119], v[118:119], 0.5, v[122:123] op_sel_hi:[1,0,1]
	global_store_dwordx4 v[154:155], v[118:121], off offset:512
	global_load_dwordx4 v[118:121], v[152:153], off offset:576
	v_pk_mul_f32 v[116:117], v[116:117], v[128:129]
	v_pk_mul_f32 v[114:115], v[114:115], v[126:127]
	s_waitcnt vmcnt(0) lgkmcnt(0)
	v_pk_fma_f32 v[116:117], v[116:117], 0.5, v[120:121] op_sel_hi:[1,0,1]
	v_pk_fma_f32 v[114:115], v[114:115], 0.5, v[118:119] op_sel_hi:[1,0,1]
	global_store_dwordx4 v[154:155], v[114:117], off offset:576
.LBB0_3170:
	s_or_b64 exec, exec, s[8:9]
	s_nop 0
	v_or_b32_e32 v114, 16, v134
	v_cmp_gt_i32_e32 vcc, s11, v114
	s_and_saveexec_b64 s[8:9], vcc
	s_cbranch_execz .LBB0_3172
	s_movk_i32 s11, 0x4000
	v_add_u32_e32 v115, 0xffffc012, v134
	v_mov_b32_e32 v116, s10
	v_cmp_gt_i32_e32 vcc, s11, v114
	s_mov_b32 s11, 0x9000
	v_add_u32_e32 v128, 0xffffc010, v134
	v_cndmask_b32_e32 v115, v115, v116, vcc
	v_mov_b64_e32 v[116:117], s[14:15]
	v_mad_i64_i32 v[116:117], s[24:25], v115, s11, v[116:117]
	v_ashrrev_i32_e32 v115, 31, v114
	v_lshlrev_b64 v[114:115], 12, v[114:115]
	v_mov_b32_e32 v129, 0
	s_mov_b64 s[24:25], 0x8000
	v_lshl_add_u64 v[122:123], s[6:7], 0, v[114:115]
	v_lshlrev_b64 v[114:115], 12, v[128:129]
	v_mov_b32_e32 v131, v129
	v_lshl_add_u64 v[126:127], v[116:117], 0, s[24:25]
	v_lshl_add_u64 v[114:115], s[18:19], 0, v[114:115]
	v_lshlrev_b64 v[124:125], 2, v[130:131]
	v_cndmask_b32_e32 v119, v115, v123, vcc
	v_cndmask_b32_e32 v118, v114, v122, vcc
	v_lshl_add_u64 v[114:115], v[126:127], 0, v[124:125]
	global_load_dwordx4 v[114:117], v[114:115], off
	v_lshl_add_u64 v[136:137], v[118:119], 0, v[124:125]
	global_load_dwordx4 v[118:121], v[136:137], off
	v_mov_b32_e32 v133, v129
	v_lshl_add_u64 v[138:139], v[122:123], 0, v[124:125]
	v_lshl_add_u64 v[122:123], v[132:133], 2, v[126:127]
	global_load_dwordx4 v[122:125], v[122:123], off
	v_or_b32_e32 v128, 0x80, v130
	s_waitcnt vmcnt(0) lgkmcnt(0)
	v_pk_mul_f32 v[112:113], v[112:113], v[116:117]
	v_pk_mul_f32 v[110:111], v[110:111], v[114:115]
	v_pk_fma_f32 v[112:113], v[112:113], 0.5, v[120:121] op_sel_hi:[1,0,1]
	v_pk_fma_f32 v[110:111], v[110:111], 0.5, v[118:119] op_sel_hi:[1,0,1]
	global_store_dwordx4 v[138:139], v[110:113], off
	global_load_dwordx4 v[110:113], v[136:137], off offset:64
	v_pk_mul_f32 v[108:109], v[108:109], v[124:125]
	v_pk_mul_f32 v[106:107], v[106:107], v[122:123]
	v_lshl_add_u64 v[114:115], v[128:129], 2, v[126:127]
	global_load_dwordx4 v[114:117], v[114:115], off
	v_or_b32_e32 v128, 0x90, v130
	s_waitcnt vmcnt(0) lgkmcnt(0)
	v_pk_fma_f32 v[108:109], v[108:109], 0.5, v[112:113] op_sel_hi:[1,0,1]
	v_pk_fma_f32 v[106:107], v[106:107], 0.5, v[110:111] op_sel_hi:[1,0,1]
	global_store_dwordx4 v[138:139], v[106:109], off offset:64
	global_load_dwordx4 v[106:109], v[136:137], off offset:512
	v_lshl_add_u64 v[110:111], v[128:129], 2, v[126:127]
	global_load_dwordx4 v[110:113], v[110:111], off
	v_pk_mul_f32 v[104:105], v[104:105], v[116:117]
	v_pk_mul_f32 v[102:103], v[102:103], v[114:115]
	s_waitcnt vmcnt(0) lgkmcnt(0)
	v_pk_fma_f32 v[104:105], v[104:105], 0.5, v[108:109] op_sel_hi:[1,0,1]
	v_pk_fma_f32 v[102:103], v[102:103], 0.5, v[106:107] op_sel_hi:[1,0,1]
	global_store_dwordx4 v[138:139], v[102:105], off offset:512
	global_load_dwordx4 v[102:105], v[136:137], off offset:576
	v_pk_mul_f32 v[100:101], v[100:101], v[112:113]
	v_pk_mul_f32 v[98:99], v[98:99], v[110:111]
	s_waitcnt vmcnt(0) lgkmcnt(0)
	v_pk_fma_f32 v[100:101], v[100:101], 0.5, v[104:105] op_sel_hi:[1,0,1]
	v_pk_fma_f32 v[98:99], v[98:99], 0.5, v[102:103] op_sel_hi:[1,0,1]
	global_store_dwordx4 v[138:139], v[98:101], off offset:576
.LBB0_3172:
	s_or_b64 exec, exec, s[8:9]
	s_nop 0
	v_or_b32_e32 v98, 32, v134
	s_movk_i32 s11, 0x4080
	v_cmp_gt_i32_e32 vcc, s11, v98
	s_and_saveexec_b64 s[8:9], vcc
	s_cbranch_execz .LBB0_3174
	s_movk_i32 s17, 0x4000
	v_add_u32_e32 v99, 0xffffc022, v134
	v_mov_b32_e32 v100, s10
	v_cmp_gt_i32_e32 vcc, s17, v98
	s_mov_b32 s17, 0x9000
	v_add_u32_e32 v112, 0xffffc020, v134
	v_cndmask_b32_e32 v99, v99, v100, vcc
	v_mov_b64_e32 v[100:101], s[14:15]
	v_mad_i64_i32 v[100:101], s[24:25], v99, s17, v[100:101]
	v_ashrrev_i32_e32 v99, 31, v98
	v_lshlrev_b64 v[98:99], 12, v[98:99]
	v_mov_b32_e32 v113, 0
	s_mov_b64 s[24:25], 0x8000
	v_lshl_add_u64 v[106:107], s[6:7], 0, v[98:99]
	v_lshlrev_b64 v[98:99], 12, v[112:113]
	v_mov_b32_e32 v131, v113
	v_lshl_add_u64 v[110:111], v[100:101], 0, s[24:25]
	v_lshl_add_u64 v[98:99], s[18:19], 0, v[98:99]
	v_lshlrev_b64 v[108:109], 2, v[130:131]
	v_cndmask_b32_e32 v103, v99, v107, vcc
	v_cndmask_b32_e32 v102, v98, v106, vcc
	v_lshl_add_u64 v[98:99], v[110:111], 0, v[108:109]
	global_load_dwordx4 v[98:101], v[98:99], off
	v_lshl_add_u64 v[114:115], v[102:103], 0, v[108:109]
	global_load_dwordx4 v[102:105], v[114:115], off
	v_mov_b32_e32 v133, v113
	v_lshl_add_u64 v[116:117], v[106:107], 0, v[108:109]
	v_lshl_add_u64 v[106:107], v[132:133], 2, v[110:111]
	global_load_dwordx4 v[106:109], v[106:107], off
	v_or_b32_e32 v112, 0x80, v130
	s_waitcnt vmcnt(0) lgkmcnt(0)
	v_pk_mul_f32 v[96:97], v[96:97], v[100:101]
	v_pk_mul_f32 v[94:95], v[94:95], v[98:99]
	v_pk_fma_f32 v[96:97], v[96:97], 0.5, v[104:105] op_sel_hi:[1,0,1]
	v_pk_fma_f32 v[94:95], v[94:95], 0.5, v[102:103] op_sel_hi:[1,0,1]
	global_store_dwordx4 v[116:117], v[94:97], off
	global_load_dwordx4 v[94:97], v[114:115], off offset:64
	v_pk_mul_f32 v[92:93], v[92:93], v[108:109]
	v_pk_mul_f32 v[90:91], v[90:91], v[106:107]
	v_lshl_add_u64 v[98:99], v[112:113], 2, v[110:111]
	global_load_dwordx4 v[98:101], v[98:99], off
	v_or_b32_e32 v112, 0x90, v130
	s_waitcnt vmcnt(0) lgkmcnt(0)
	v_pk_fma_f32 v[92:93], v[92:93], 0.5, v[96:97] op_sel_hi:[1,0,1]
	v_pk_fma_f32 v[90:91], v[90:91], 0.5, v[94:95] op_sel_hi:[1,0,1]
	global_store_dwordx4 v[116:117], v[90:93], off offset:64
	global_load_dwordx4 v[90:93], v[114:115], off offset:512
	v_lshl_add_u64 v[94:95], v[112:113], 2, v[110:111]
	global_load_dwordx4 v[94:97], v[94:95], off
	v_pk_mul_f32 v[88:89], v[88:89], v[100:101]
	v_pk_mul_f32 v[86:87], v[86:87], v[98:99]
	s_waitcnt vmcnt(0) lgkmcnt(0)
	v_pk_fma_f32 v[88:89], v[88:89], 0.5, v[92:93] op_sel_hi:[1,0,1]
	v_pk_fma_f32 v[86:87], v[86:87], 0.5, v[90:91] op_sel_hi:[1,0,1]
	global_store_dwordx4 v[116:117], v[86:89], off offset:512
	global_load_dwordx4 v[86:89], v[114:115], off offset:576
	v_pk_mul_f32 v[84:85], v[84:85], v[96:97]
	v_pk_mul_f32 v[82:83], v[82:83], v[94:95]
	s_waitcnt vmcnt(0) lgkmcnt(0)
	v_pk_fma_f32 v[84:85], v[84:85], 0.5, v[88:89] op_sel_hi:[1,0,1]
	v_pk_fma_f32 v[82:83], v[82:83], 0.5, v[86:87] op_sel_hi:[1,0,1]
	global_store_dwordx4 v[116:117], v[82:85], off offset:576
.LBB0_3174:
	s_or_b64 exec, exec, s[8:9]
	s_nop 0
	v_or_b32_e32 v82, 48, v134
	v_cmp_gt_i32_e32 vcc, s11, v82
	s_and_saveexec_b64 s[8:9], vcc
	s_cbranch_execz .LBB0_3176
	s_movk_i32 s11, 0x4000
	v_add_u32_e32 v83, 0xffffc032, v134
	v_mov_b32_e32 v84, s10
	v_cmp_gt_i32_e32 vcc, s11, v82
	s_mov_b32 s10, 0x9000
	v_add_u32_e32 v96, 0xffffc030, v134
	v_cndmask_b32_e32 v83, v83, v84, vcc
	v_mov_b64_e32 v[84:85], s[14:15]
	v_mad_i64_i32 v[84:85], s[10:11], v83, s10, v[84:85]
	v_ashrrev_i32_e32 v83, 31, v82
	v_lshlrev_b64 v[82:83], 12, v[82:83]
	v_mov_b32_e32 v97, 0
	s_mov_b64 s[10:11], 0x8000
	v_lshl_add_u64 v[90:91], s[6:7], 0, v[82:83]
	v_lshlrev_b64 v[82:83], 12, v[96:97]
	v_mov_b32_e32 v131, v97
	v_lshl_add_u64 v[94:95], v[84:85], 0, s[10:11]
	v_lshl_add_u64 v[82:83], s[18:19], 0, v[82:83]
	v_lshlrev_b64 v[92:93], 2, v[130:131]
	v_cndmask_b32_e32 v87, v83, v91, vcc
	v_cndmask_b32_e32 v86, v82, v90, vcc
	v_lshl_add_u64 v[82:83], v[94:95], 0, v[92:93]
	global_load_dwordx4 v[82:85], v[82:83], off
	v_lshl_add_u64 v[98:99], v[86:87], 0, v[92:93]
	global_load_dwordx4 v[86:89], v[98:99], off
	v_mov_b32_e32 v133, v97
	v_lshl_add_u64 v[100:101], v[90:91], 0, v[92:93]
	v_lshl_add_u64 v[90:91], v[132:133], 2, v[94:95]
	global_load_dwordx4 v[90:93], v[90:91], off
	v_or_b32_e32 v96, 0x80, v130
	s_waitcnt vmcnt(0) lgkmcnt(0)
	v_pk_mul_f32 v[80:81], v[80:81], v[84:85]
	v_pk_mul_f32 v[78:79], v[78:79], v[82:83]
	v_pk_fma_f32 v[80:81], v[80:81], 0.5, v[88:89] op_sel_hi:[1,0,1]
	v_pk_fma_f32 v[78:79], v[78:79], 0.5, v[86:87] op_sel_hi:[1,0,1]
	global_store_dwordx4 v[100:101], v[78:81], off
	global_load_dwordx4 v[78:81], v[98:99], off offset:64
	v_pk_mul_f32 v[76:77], v[76:77], v[92:93]
	v_pk_mul_f32 v[74:75], v[74:75], v[90:91]
	v_lshl_add_u64 v[82:83], v[96:97], 2, v[94:95]
	global_load_dwordx4 v[82:85], v[82:83], off
	v_or_b32_e32 v96, 0x90, v130
	s_waitcnt vmcnt(0) lgkmcnt(0)
	v_pk_fma_f32 v[76:77], v[76:77], 0.5, v[80:81] op_sel_hi:[1,0,1]
	v_pk_fma_f32 v[74:75], v[74:75], 0.5, v[78:79] op_sel_hi:[1,0,1]
	global_store_dwordx4 v[100:101], v[74:77], off offset:64
	global_load_dwordx4 v[74:77], v[98:99], off offset:512
	v_lshl_add_u64 v[78:79], v[96:97], 2, v[94:95]
	global_load_dwordx4 v[78:81], v[78:79], off
	v_pk_mul_f32 v[72:73], v[72:73], v[84:85]
	v_pk_mul_f32 v[70:71], v[70:71], v[82:83]
	s_waitcnt vmcnt(0) lgkmcnt(0)
	v_pk_fma_f32 v[72:73], v[72:73], 0.5, v[76:77] op_sel_hi:[1,0,1]
	v_pk_fma_f32 v[70:71], v[70:71], 0.5, v[74:75] op_sel_hi:[1,0,1]
	global_store_dwordx4 v[100:101], v[70:73], off offset:512
	global_load_dwordx4 v[70:73], v[98:99], off offset:576
	v_pk_mul_f32 v[68:69], v[68:69], v[80:81]
	v_pk_mul_f32 v[66:67], v[66:67], v[78:79]
	s_waitcnt vmcnt(0) lgkmcnt(0)
	v_pk_fma_f32 v[68:69], v[68:69], 0.5, v[72:73] op_sel_hi:[1,0,1]
	v_pk_fma_f32 v[66:67], v[66:67], 0.5, v[70:71] op_sel_hi:[1,0,1]
	global_store_dwordx4 v[100:101], v[66:69], off offset:576
.LBB0_3176:
	s_or_b64 exec, exec, s[8:9]
	s_addk_i32 s5, 0x4080
	s_movk_i32 s10, 0x4080
	v_or_b32_e32 v66, s5, v1
	s_ashr_i32 s5, s5, 13
	v_cmp_gt_i32_e32 vcc, s10, v66
	s_and_saveexec_b64 s[8:9], vcc
	s_cbranch_execz .LBB0_3178
	s_movk_i32 s11, 0x4000
	v_add_u32_e32 v1, 0xffffc002, v66
	v_mov_b32_e32 v67, s5
	v_cmp_gt_i32_e32 vcc, s11, v66
	s_mov_b32 s11, 0x9000
	v_mov_b64_e32 v[68:69], s[14:15]
	v_cndmask_b32_e32 v1, v1, v67, vcc
	v_mad_i64_i32 v[68:69], s[24:25], v1, s11, v[68:69]
	s_mov_b64 s[24:25], 0x8000
	v_ashrrev_i32_e32 v67, 31, v66
	v_lshl_add_u64 v[80:81], v[68:69], 0, s[24:25]
	v_lshlrev_b64 v[68:69], 12, v[66:67]
	v_add_u32_e32 v82, 0xffffc000, v66
	v_mov_b32_e32 v83, 0
	v_lshl_add_u64 v[76:77], s[6:7], 0, v[68:69]
	v_lshlrev_b64 v[68:69], 12, v[82:83]
	v_mov_b32_e32 v131, v83
	v_lshl_add_u64 v[68:69], s[18:19], 0, v[68:69]
	v_lshlrev_b64 v[78:79], 2, v[130:131]
	v_cndmask_b32_e32 v73, v69, v77, vcc
	v_cndmask_b32_e32 v72, v68, v76, vcc
	v_lshl_add_u64 v[68:69], v[80:81], 0, v[78:79]
	global_load_dwordx4 v[68:71], v[68:69], off
	v_lshl_add_u64 v[84:85], v[72:73], 0, v[78:79]
	global_load_dwordx4 v[72:75], v[84:85], off
	v_mov_b32_e32 v133, v83
	v_lshl_add_u64 v[86:87], v[76:77], 0, v[78:79]
	v_lshl_add_u64 v[76:77], v[132:133], 2, v[80:81]
	global_load_dwordx4 v[76:79], v[76:77], off
	v_or_b32_e32 v82, 0x80, v130
	s_waitcnt vmcnt(0) lgkmcnt(0)
	v_pk_mul_f32 v[64:65], v[64:65], v[70:71]
	v_pk_mul_f32 v[62:63], v[62:63], v[68:69]
	v_pk_fma_f32 v[64:65], v[64:65], 0.5, v[74:75] op_sel_hi:[1,0,1]
	v_pk_fma_f32 v[62:63], v[62:63], 0.5, v[72:73] op_sel_hi:[1,0,1]
	global_store_dwordx4 v[86:87], v[62:65], off
	global_load_dwordx4 v[62:65], v[84:85], off offset:64
	v_pk_mul_f32 v[60:61], v[60:61], v[78:79]
	v_pk_mul_f32 v[58:59], v[58:59], v[76:77]
	v_lshl_add_u64 v[68:69], v[82:83], 2, v[80:81]
	global_load_dwordx4 v[68:71], v[68:69], off
	v_or_b32_e32 v82, 0x90, v130
	s_waitcnt vmcnt(0) lgkmcnt(0)
	v_pk_fma_f32 v[60:61], v[60:61], 0.5, v[64:65] op_sel_hi:[1,0,1]
	v_pk_fma_f32 v[58:59], v[58:59], 0.5, v[62:63] op_sel_hi:[1,0,1]
	global_store_dwordx4 v[86:87], v[58:61], off offset:64
	global_load_dwordx4 v[58:61], v[84:85], off offset:512
	v_lshl_add_u64 v[62:63], v[82:83], 2, v[80:81]
	global_load_dwordx4 v[62:65], v[62:63], off
	v_pk_mul_f32 v[56:57], v[56:57], v[70:71]
	v_pk_mul_f32 v[54:55], v[54:55], v[68:69]
	s_waitcnt vmcnt(0) lgkmcnt(0)
	v_pk_fma_f32 v[56:57], v[56:57], 0.5, v[60:61] op_sel_hi:[1,0,1]
	v_pk_fma_f32 v[54:55], v[54:55], 0.5, v[58:59] op_sel_hi:[1,0,1]
	global_store_dwordx4 v[86:87], v[54:57], off offset:512
	global_load_dwordx4 v[54:57], v[84:85], off offset:576
	v_pk_mul_f32 v[52:53], v[52:53], v[64:65]
	v_pk_mul_f32 v[50:51], v[50:51], v[62:63]
	s_waitcnt vmcnt(0) lgkmcnt(0)
	v_pk_fma_f32 v[52:53], v[52:53], 0.5, v[56:57] op_sel_hi:[1,0,1]
	v_pk_fma_f32 v[50:51], v[50:51], 0.5, v[54:55] op_sel_hi:[1,0,1]
	global_store_dwordx4 v[86:87], v[50:53], off offset:576
.LBB0_3178:
	s_or_b64 exec, exec, s[8:9]
	s_nop 0
	v_or_b32_e32 v50, 16, v66
	v_cmp_gt_i32_e32 vcc, s10, v50
	s_and_saveexec_b64 s[8:9], vcc
	s_cbranch_execz .LBB0_3180
	s_movk_i32 s10, 0x4000
	v_add_u32_e32 v1, 0xffffc012, v66
	v_mov_b32_e32 v51, s5
	v_cmp_gt_i32_e32 vcc, s10, v50
	s_mov_b32 s10, 0x9000
	v_mov_b64_e32 v[52:53], s[14:15]
	v_cndmask_b32_e32 v1, v1, v51, vcc
	v_ashrrev_i32_e32 v51, 31, v50
	v_mad_i64_i32 v[52:53], s[10:11], v1, s10, v[52:53]
	v_lshlrev_b64 v[50:51], 12, v[50:51]
	v_add_u32_e32 v64, 0xffffc010, v66
	v_mov_b32_e32 v65, 0
	s_mov_b64 s[10:11], 0x8000
	v_lshl_add_u64 v[58:59], s[6:7], 0, v[50:51]
	v_lshlrev_b64 v[50:51], 12, v[64:65]
	v_mov_b32_e32 v131, v65
	v_lshl_add_u64 v[62:63], v[52:53], 0, s[10:11]
	v_lshl_add_u64 v[50:51], s[18:19], 0, v[50:51]
	v_lshlrev_b64 v[60:61], 2, v[130:131]
	v_cndmask_b32_e32 v55, v51, v59, vcc
	v_cndmask_b32_e32 v54, v50, v58, vcc
	v_lshl_add_u64 v[50:51], v[62:63], 0, v[60:61]
	global_load_dwordx4 v[50:53], v[50:51], off
	v_lshl_add_u64 v[68:69], v[54:55], 0, v[60:61]
	global_load_dwordx4 v[54:57], v[68:69], off
	v_mov_b32_e32 v133, v65
	v_lshl_add_u64 v[70:71], v[58:59], 0, v[60:61]
	v_lshl_add_u64 v[58:59], v[132:133], 2, v[62:63]
	global_load_dwordx4 v[58:61], v[58:59], off
	v_or_b32_e32 v64, 0x80, v130
	s_waitcnt vmcnt(0) lgkmcnt(0)
	v_pk_mul_f32 v[48:49], v[48:49], v[52:53]
	v_pk_mul_f32 v[46:47], v[46:47], v[50:51]
	v_pk_fma_f32 v[48:49], v[48:49], 0.5, v[56:57] op_sel_hi:[1,0,1]
	v_pk_fma_f32 v[46:47], v[46:47], 0.5, v[54:55] op_sel_hi:[1,0,1]
	global_store_dwordx4 v[70:71], v[46:49], off
	global_load_dwordx4 v[46:49], v[68:69], off offset:64
	v_pk_mul_f32 v[44:45], v[44:45], v[60:61]
	v_pk_mul_f32 v[42:43], v[42:43], v[58:59]
	v_lshl_add_u64 v[50:51], v[64:65], 2, v[62:63]
	global_load_dwordx4 v[50:53], v[50:51], off
	v_or_b32_e32 v64, 0x90, v130
	s_waitcnt vmcnt(0) lgkmcnt(0)
	v_pk_fma_f32 v[44:45], v[44:45], 0.5, v[48:49] op_sel_hi:[1,0,1]
	v_pk_fma_f32 v[42:43], v[42:43], 0.5, v[46:47] op_sel_hi:[1,0,1]
	global_store_dwordx4 v[70:71], v[42:45], off offset:64
	global_load_dwordx4 v[42:45], v[68:69], off offset:512
	v_lshl_add_u64 v[46:47], v[64:65], 2, v[62:63]
	global_load_dwordx4 v[46:49], v[46:47], off
	v_pk_mul_f32 v[40:41], v[40:41], v[52:53]
	v_pk_mul_f32 v[38:39], v[38:39], v[50:51]
	s_waitcnt vmcnt(0) lgkmcnt(0)
	v_pk_fma_f32 v[40:41], v[40:41], 0.5, v[44:45] op_sel_hi:[1,0,1]
	v_pk_fma_f32 v[38:39], v[38:39], 0.5, v[42:43] op_sel_hi:[1,0,1]
	global_store_dwordx4 v[70:71], v[38:41], off offset:512
	global_load_dwordx4 v[38:41], v[68:69], off offset:576
	v_pk_mul_f32 v[36:37], v[36:37], v[48:49]
	v_pk_mul_f32 v[34:35], v[34:35], v[46:47]
	s_waitcnt vmcnt(0) lgkmcnt(0)
	v_pk_fma_f32 v[36:37], v[36:37], 0.5, v[40:41] op_sel_hi:[1,0,1]
	v_pk_fma_f32 v[34:35], v[34:35], 0.5, v[38:39] op_sel_hi:[1,0,1]
	global_store_dwordx4 v[70:71], v[34:37], off offset:576
.LBB0_3180:
	s_or_b64 exec, exec, s[8:9]
	s_nop 0
	v_or_b32_e32 v34, 32, v66
	s_movk_i32 s10, 0x4080
	v_cmp_gt_i32_e32 vcc, s10, v34
	s_and_saveexec_b64 s[8:9], vcc
	s_cbranch_execz .LBB0_3182
	s_movk_i32 s11, 0x4000
	v_add_u32_e32 v1, 0xffffc022, v66
	v_mov_b32_e32 v35, s5
	v_cmp_gt_i32_e32 vcc, s11, v34
	s_mov_b32 s11, 0x9000
	v_mov_b64_e32 v[36:37], s[14:15]
	v_cndmask_b32_e32 v1, v1, v35, vcc
	v_ashrrev_i32_e32 v35, 31, v34
	v_mad_i64_i32 v[36:37], s[24:25], v1, s11, v[36:37]
	v_lshlrev_b64 v[34:35], 12, v[34:35]
	v_add_u32_e32 v48, 0xffffc020, v66
	v_mov_b32_e32 v49, 0
	s_mov_b64 s[24:25], 0x8000
	v_lshl_add_u64 v[42:43], s[6:7], 0, v[34:35]
	v_lshlrev_b64 v[34:35], 12, v[48:49]
	v_mov_b32_e32 v131, v49
	v_lshl_add_u64 v[46:47], v[36:37], 0, s[24:25]
	v_lshl_add_u64 v[34:35], s[18:19], 0, v[34:35]
	v_lshlrev_b64 v[44:45], 2, v[130:131]
	v_cndmask_b32_e32 v39, v35, v43, vcc
	v_cndmask_b32_e32 v38, v34, v42, vcc
	v_lshl_add_u64 v[34:35], v[46:47], 0, v[44:45]
	global_load_dwordx4 v[34:37], v[34:35], off
	v_lshl_add_u64 v[50:51], v[38:39], 0, v[44:45]
	global_load_dwordx4 v[38:41], v[50:51], off
	v_mov_b32_e32 v133, v49
	v_lshl_add_u64 v[52:53], v[42:43], 0, v[44:45]
	v_lshl_add_u64 v[42:43], v[132:133], 2, v[46:47]
	global_load_dwordx4 v[42:45], v[42:43], off
	v_or_b32_e32 v48, 0x80, v130
	s_waitcnt vmcnt(0) lgkmcnt(0)
	v_pk_mul_f32 v[32:33], v[32:33], v[36:37]
	v_pk_mul_f32 v[30:31], v[30:31], v[34:35]
	v_pk_fma_f32 v[32:33], v[32:33], 0.5, v[40:41] op_sel_hi:[1,0,1]
	v_pk_fma_f32 v[30:31], v[30:31], 0.5, v[38:39] op_sel_hi:[1,0,1]
	global_store_dwordx4 v[52:53], v[30:33], off
	global_load_dwordx4 v[30:33], v[50:51], off offset:64
	v_pk_mul_f32 v[28:29], v[28:29], v[44:45]
	v_pk_mul_f32 v[26:27], v[26:27], v[42:43]
	v_lshl_add_u64 v[34:35], v[48:49], 2, v[46:47]
	global_load_dwordx4 v[34:37], v[34:35], off
	v_or_b32_e32 v48, 0x90, v130
	s_waitcnt vmcnt(0) lgkmcnt(0)
	v_pk_fma_f32 v[28:29], v[28:29], 0.5, v[32:33] op_sel_hi:[1,0,1]
	v_pk_fma_f32 v[26:27], v[26:27], 0.5, v[30:31] op_sel_hi:[1,0,1]
	global_store_dwordx4 v[52:53], v[26:29], off offset:64
	global_load_dwordx4 v[26:29], v[50:51], off offset:512
	v_lshl_add_u64 v[30:31], v[48:49], 2, v[46:47]
	global_load_dwordx4 v[30:33], v[30:31], off
	v_pk_mul_f32 v[24:25], v[24:25], v[36:37]
	v_pk_mul_f32 v[22:23], v[22:23], v[34:35]
	s_waitcnt vmcnt(0) lgkmcnt(0)
	v_pk_fma_f32 v[24:25], v[24:25], 0.5, v[28:29] op_sel_hi:[1,0,1]
	v_pk_fma_f32 v[22:23], v[22:23], 0.5, v[26:27] op_sel_hi:[1,0,1]
	global_store_dwordx4 v[52:53], v[22:25], off offset:512
	global_load_dwordx4 v[22:25], v[50:51], off offset:576
	v_pk_mul_f32 v[20:21], v[20:21], v[32:33]
	v_pk_mul_f32 v[18:19], v[18:19], v[30:31]
	s_waitcnt vmcnt(0) lgkmcnt(0)
	v_pk_fma_f32 v[20:21], v[20:21], 0.5, v[24:25] op_sel_hi:[1,0,1]
	v_pk_fma_f32 v[18:19], v[18:19], 0.5, v[22:23] op_sel_hi:[1,0,1]
	global_store_dwordx4 v[52:53], v[18:21], off offset:576
.LBB0_3182:
	s_or_b64 exec, exec, s[8:9]
	s_nop 0
	v_or_b32_e32 v18, 48, v66
	v_cmp_gt_i32_e32 vcc, s10, v18
	s_and_saveexec_b64 s[8:9], vcc
	s_cbranch_execz .LBB0_3184
	s_movk_i32 s10, 0x4000
	v_add_u32_e32 v1, 0xffffc032, v66
	v_mov_b32_e32 v19, s5
	v_cmp_gt_i32_e32 vcc, s10, v18
	s_mov_b32 s5, 0x9000
	v_mov_b64_e32 v[20:21], s[14:15]
	v_cndmask_b32_e32 v1, v1, v19, vcc
	v_ashrrev_i32_e32 v19, 31, v18
	v_mad_i64_i32 v[20:21], s[10:11], v1, s5, v[20:21]
	v_lshlrev_b64 v[18:19], 12, v[18:19]
	v_add_u32_e32 v32, 0xffffc030, v66
	v_mov_b32_e32 v33, 0
	s_mov_b64 s[10:11], 0x8000
	v_lshl_add_u64 v[26:27], s[6:7], 0, v[18:19]
	v_lshlrev_b64 v[18:19], 12, v[32:33]
	v_mov_b32_e32 v131, v33
	v_lshl_add_u64 v[30:31], v[20:21], 0, s[10:11]
	v_lshl_add_u64 v[18:19], s[18:19], 0, v[18:19]
	v_lshlrev_b64 v[28:29], 2, v[130:131]
	v_cndmask_b32_e32 v23, v19, v27, vcc
	v_cndmask_b32_e32 v22, v18, v26, vcc
	v_lshl_add_u64 v[18:19], v[30:31], 0, v[28:29]
	global_load_dwordx4 v[18:21], v[18:19], off
	v_lshl_add_u64 v[34:35], v[22:23], 0, v[28:29]
	global_load_dwordx4 v[22:25], v[34:35], off
	v_mov_b32_e32 v133, v33
	v_lshl_add_u64 v[36:37], v[26:27], 0, v[28:29]
	v_lshl_add_u64 v[26:27], v[132:133], 2, v[30:31]
	global_load_dwordx4 v[26:29], v[26:27], off
	v_or_b32_e32 v32, 0x80, v130
	s_waitcnt vmcnt(0) lgkmcnt(0)
	v_pk_mul_f32 v[16:17], v[16:17], v[20:21]
	v_pk_mul_f32 v[14:15], v[14:15], v[18:19]
	v_pk_fma_f32 v[16:17], v[16:17], 0.5, v[24:25] op_sel_hi:[1,0,1]
	v_pk_fma_f32 v[14:15], v[14:15], 0.5, v[22:23] op_sel_hi:[1,0,1]
	global_store_dwordx4 v[36:37], v[14:17], off
	global_load_dwordx4 v[14:17], v[34:35], off offset:64
	v_pk_mul_f32 v[12:13], v[12:13], v[28:29]
	v_pk_mul_f32 v[10:11], v[10:11], v[26:27]
	v_lshl_add_u64 v[18:19], v[32:33], 2, v[30:31]
	global_load_dwordx4 v[18:21], v[18:19], off
	v_or_b32_e32 v32, 0x90, v130
	s_waitcnt vmcnt(0) lgkmcnt(0)
	v_pk_fma_f32 v[12:13], v[12:13], 0.5, v[16:17] op_sel_hi:[1,0,1]
	v_pk_fma_f32 v[10:11], v[10:11], 0.5, v[14:15] op_sel_hi:[1,0,1]
	global_store_dwordx4 v[36:37], v[10:13], off offset:64
	global_load_dwordx4 v[10:13], v[34:35], off offset:512
	v_lshl_add_u64 v[14:15], v[32:33], 2, v[30:31]
	global_load_dwordx4 v[14:17], v[14:15], off
	v_pk_mul_f32 v[8:9], v[8:9], v[20:21]
	v_pk_mul_f32 v[6:7], v[6:7], v[18:19]
	s_waitcnt vmcnt(0) lgkmcnt(0)
	v_pk_fma_f32 v[8:9], v[8:9], 0.5, v[12:13] op_sel_hi:[1,0,1]
	v_pk_fma_f32 v[6:7], v[6:7], 0.5, v[10:11] op_sel_hi:[1,0,1]
	global_store_dwordx4 v[36:37], v[6:9], off offset:512
	global_load_dwordx4 v[6:9], v[34:35], off offset:576
	v_pk_mul_f32 v[4:5], v[4:5], v[16:17]
	v_pk_mul_f32 v[2:3], v[2:3], v[14:15]
	s_waitcnt vmcnt(0) lgkmcnt(0)
	v_pk_fma_f32 v[4:5], v[4:5], 0.5, v[8:9] op_sel_hi:[1,0,1]
	v_pk_fma_f32 v[2:3], v[2:3], 0.5, v[6:7] op_sel_hi:[1,0,1]
	global_store_dwordx4 v[36:37], v[2:5], off offset:576

.LBB0_3192:
	s_or_b64 exec, exec, s[6:7]
	v_mov_b32_e32 v1, v0
	v_mov_b64_e32 v[2:3], s[0:1]
	s_barrier
	global_load_dwordx2 v[2:3], v[2:3], off offset:88 sc0 sc1
	s_waitcnt vmcnt(0)
	v_readfirstlane_b32 s5, v1
	s_ashr_i32 s6, s5, 6
	s_cmp_gt_i32 s6, 7
	s_cbranch_scc1 .LBB0_3195
	v_and_b32_e32 v21, 63, v1
	v_mov_b32_e32 v91, 0
	v_lshlrev_b32_e32 v90, 4, v21
	s_waitcnt lgkmcnt(0)
	v_lshl_add_u64 v[2:3], v[2:3], 0, v[90:91]
	s_movk_i32 s5, 0x3000
	v_add_co_u32_e32 v18, vcc, s5, v2
	v_mbcnt_lo_u32_b32 v1, -1, 0
	s_nop 0
	v_addc_co_u32_e32 v19, vcc, 0, v3, vcc
	global_load_dwordx4 v[2:5], v[18:19], off
	global_load_dwordx4 v[6:9], v[18:19], off offset:1024
	global_load_dwordx4 v[10:13], v[18:19], off offset:2048
	global_load_dwordx4 v[14:17], v[18:19], off offset:3072
	v_mbcnt_hi_u32_b32 v18, -1, v1
	v_and_b32_e32 v1, 64, v18
	v_add_u32_e32 v19, 64, v1
	v_xor_b32_e32 v1, 1, v18
	v_cmp_lt_i32_e32 vcc, v1, v19
	v_xor_b32_e32 v20, 2, v18
	s_lshl_b32 s7, s16, 5
	v_cndmask_b32_e32 v1, v18, v1, vcc
	v_cmp_lt_i32_e32 vcc, v20, v19
	s_lshl_b32 s6, s6, 2
	s_add_i32 s6, s7, s6
	v_cndmask_b32_e32 v20, v18, v20, vcc
	v_lshlrev_b32_e32 v148, 2, v20
	v_xor_b32_e32 v20, 4, v18
	v_cmp_lt_i32_e32 vcc, v20, v19
	s_add_i32 s24, s6, 0x2080
	s_ashr_i32 s25, s24, 31
	v_cndmask_b32_e32 v20, v18, v20, vcc
	v_lshlrev_b32_e32 v149, 2, v20
	v_xor_b32_e32 v20, 8, v18
	v_cmp_lt_i32_e32 vcc, v20, v19
	s_add_i32 s5, s7, 0x20a0
	s_lshl_b64 s[6:7], s[24:25], 11
	v_cndmask_b32_e32 v20, v18, v20, vcc
	v_lshlrev_b32_e32 v150, 2, v20
	v_xor_b32_e32 v20, 16, v18
	v_cmp_lt_i32_e32 vcc, v20, v19
	v_lshl_or_b32 v92, v21, 3, s6
	v_mov_b32_e32 v93, s7
	v_cndmask_b32_e32 v20, v18, v20, vcc
	v_lshlrev_b32_e32 v151, 2, v20
	v_xor_b32_e32 v20, 32, v18
	v_cmp_lt_i32_e32 vcc, v20, v19
	s_lshl_b64 s[6:7], s[24:25], 12
	v_lshlrev_b32_e32 v1, 2, v1
	v_cndmask_b32_e32 v18, v18, v20, vcc
	v_lshlrev_b32_e32 v152, 2, v18
	v_lshlrev_b32_e32 v18, 2, v21
	v_or_b32_e32 v20, 0x100, v18
	v_or_b32_e32 v22, 0x200, v18
	v_or_b32_e32 v24, 0x300, v18
	v_or_b32_e32 v94, s6, v90
	v_mov_b32_e32 v95, s7
	v_mov_b32_e32 v153, 0x358637bd
	s_mov_b32 s17, 0xf800000
	v_mov_b32_e32 v154, 0x260
	v_lshlrev_b32_e32 v90, 2, v18
	s_movk_i32 s25, 0x7fff
	s_mov_b32 s28, 0xffff0000
	s_mov_b32 s29, 0xba00000
	v_lshlrev_b32_e32 v96, 2, v20
	v_lshlrev_b32_e32 v98, 2, v22
	v_mov_b32_e32 v99, v91
	v_lshlrev_b32_e32 v100, 2, v24
	v_mov_b32_e32 v101, v91
	s_mov_b32 s30, 0xba01000
	s_mov_b64 s[26:27], 0x10000
	s_mov_b64 s[38:39], 0x20000
	v_mov_b32_e32 v97, v91
.LBB0_3194:
	v_lshl_add_u64 v[18:19], s[12:13], 0, v[94:95]
	v_lshl_add_u64 v[22:23], s[12:13], 0, v[92:93]
	v_add_co_u32_e32 v20, vcc, 0x7800000, v18
	v_add_co_u32_e64 v102, s[6:7], s29, v22
	s_nop 0
	v_addc_co_u32_e32 v21, vcc, 0, v19, vcc
	v_addc_co_u32_e64 v103, s[6:7], 0, v23, s[6:7]
	v_add_co_u32_e64 v104, s[6:7], s30, v22
	v_add_co_u32_e32 v22, vcc, 0x7801000, v18
	s_nop 0
	v_addc_co_u32_e64 v105, s[6:7], 0, v23, s[6:7]
	global_load_dwordx4 v[78:81], v[20:21], off
	global_load_dwordx4 v[74:77], v[20:21], off offset:1024
	global_load_dwordx4 v[70:73], v[20:21], off offset:2048
	global_load_dwordx4 v[66:69], v[20:21], off offset:3072
	v_addc_co_u32_e32 v23, vcc, 0, v19, vcc
	v_add_co_u32_e32 v20, vcc, 0x7802000, v18
	global_load_dwordx4 v[62:65], v[22:23], off
	global_load_dwordx4 v[58:61], v[22:23], off offset:1024
	global_load_dwordx4 v[54:57], v[22:23], off offset:2048
	global_load_dwordx4 v[50:53], v[22:23], off offset:3072
	v_addc_co_u32_e32 v21, vcc, 0, v19, vcc
	global_load_dwordx4 v[46:49], v[20:21], off
	global_load_dwordx4 v[42:45], v[20:21], off offset:1024
	global_load_dwordx4 v[38:41], v[20:21], off offset:2048
	global_load_dwordx4 v[34:37], v[20:21], off offset:3072
	v_add_co_u32_e32 v82, vcc, 0x7803000, v18
	s_ashr_i32 s8, s24, 13
	s_nop 0
	v_addc_co_u32_e32 v83, vcc, 0, v19, vcc
	global_load_dwordx4 v[30:33], v[82:83], off
	global_load_dwordx4 v[26:29], v[82:83], off offset:1024
	global_load_dwordx4 v[22:25], v[82:83], off offset:2048
	global_load_dwordx4 v[18:21], v[82:83], off offset:3072
	s_add_i32 s9, s24, 0xffffc002
	s_cmpk_lt_i32 s24, 0x4000
	s_cselect_b32 s6, s8, s9
	s_addk_i32 s6, 0x82
	s_mul_hi_i32 s7, s6, 0x9000
	s_mul_i32 s6, s6, 0x9000
	s_add_u32 s6, s14, s6
	s_addc_u32 s7, s15, s7
	s_add_u32 s10, s6, 0x1000
	s_addc_u32 s11, s7, 0
	v_lshl_add_u64 v[124:125], s[6:7], 0, v[90:91]
	v_lshl_add_u64 v[86:87], s[10:11], 0, v[90:91]
	global_load_dwordx4 v[82:85], v[124:125], off
	s_add_i32 s6, s24, 0xffffc003
	global_load_dwordx4 v[86:89], v[86:87], off
	s_cmpk_lt_i32 s24, 0x3fff
	s_cselect_b32 s6, s8, s6
	s_addk_i32 s6, 0x82
	s_mul_hi_i32 s7, s6, 0x9000
	s_mul_i32 s6, s6, 0x9000
	s_add_u32 s6, s14, s6
	s_addc_u32 s7, s15, s7
	v_lshl_add_u64 v[134:135], s[10:11], 0, v[96:97]
	v_lshl_add_u64 v[130:131], s[10:11], 0, v[98:99]
	v_lshl_add_u64 v[128:129], s[10:11], 0, v[100:101]
	s_add_u32 s10, s6, 0x1000
	v_lshl_add_u64 v[110:111], s[6:7], 0, v[90:91]
	s_addc_u32 s11, s7, 0
	s_add_i32 s6, s24, 0xffffc004
	s_cmpk_lt_i32 s24, 0x3ffe
	s_cselect_b32 s6, s8, s6
	s_addk_i32 s6, 0x82
	s_mul_hi_i32 s7, s6, 0x9000
	s_mul_i32 s6, s6, 0x9000
	v_lshl_add_u64 v[126:127], s[10:11], 0, v[90:91]
	v_lshl_add_u64 v[120:121], s[10:11], 0, v[96:97]
	v_lshl_add_u64 v[116:117], s[10:11], 0, v[98:99]
	v_lshl_add_u64 v[112:113], s[10:11], 0, v[100:101]
	s_add_u32 s10, s14, s6
	s_addc_u32 s11, s15, s7
	s_add_u32 s6, s10, 0x1000
	s_addc_u32 s7, s11, 0
	s_add_i32 s9, s24, 0xffffc005
	s_cmpk_lt_i32 s24, 0x3ffd
	v_lshl_add_u64 v[138:139], s[6:7], 0, v[90:91]
	v_lshl_add_u64 v[136:137], s[6:7], 0, v[96:97]
	v_lshl_add_u64 v[132:133], s[6:7], 0, v[98:99]
	v_lshl_add_u64 v[122:123], s[6:7], 0, v[100:101]
	s_cselect_b32 s6, s8, s9
	s_addk_i32 s6, 0x82
	s_mul_hi_i32 s7, s6, 0x9000
	s_mul_i32 s6, s6, 0x9000
	s_add_u32 s6, s14, s6
	s_addc_u32 s7, s15, s7
	s_add_u32 s40, s6, 0x1000
	v_lshl_add_u64 v[106:107], s[6:7], 0, v[90:91]
	s_addc_u32 s41, s7, 0
	v_lshl_add_u64 v[108:109], s[10:11], 0, v[90:91]
	v_lshl_add_u64 v[118:119], s[40:41], 0, v[90:91]
	v_lshl_add_u64 v[114:115], s[40:41], 0, v[96:97]
	s_add_i32 s24, s24, 32
	v_lshl_add_u64 v[92:93], v[92:93], 0, s[26:27]
	s_waitcnt vmcnt(0) lgkmcnt(0)
	v_pk_mul_f32 v[140:141], v[80:81], v[80:81]
	v_pk_mul_f32 v[142:143], v[78:79], v[78:79]
	v_pk_mul_f32 v[144:145], v[76:77], v[76:77]
	v_pk_mul_f32 v[146:147], v[74:75], v[74:75]
	v_mul_f32_e32 v156, v71, v71
	v_mul_f32_e32 v158, v73, v73
	v_pk_mov_b32 v[160:161], v[142:143], v[140:141] op_sel:[1,0]
	v_mov_b32_e32 v143, v141
	v_pk_mov_b32 v[140:141], v[146:147], v[144:145] op_sel:[1,0]
	v_mov_b32_e32 v147, v145
	v_mul_f32_e32 v169, v68, v68
	v_mul_f32_e32 v171, v69, v69
	v_pk_fma_f32 v[144:145], v[70:71], v[70:71], v[156:157] op_sel_hi:[1,1,0]
	v_pk_fma_f32 v[156:157], v[72:73], v[72:73], v[158:159] op_sel_hi:[1,1,0]
	v_pk_mul_f32 v[158:159], v[64:65], v[64:65]
	v_pk_mul_f32 v[162:163], v[62:63], v[62:63]
	v_pk_mul_f32 v[164:165], v[60:61], v[60:61]
	v_pk_mul_f32 v[166:167], v[58:59], v[58:59]
	v_mul_f32_e32 v168, v55, v55
	v_mul_f32_e32 v170, v57, v57
	v_pk_add_f32 v[142:143], v[160:161], v[142:143]
	v_pk_add_f32 v[140:141], v[140:141], v[146:147]
	v_mul_f32_e32 v155, v66, v66
	v_mul_f32_e32 v179, v67, v67
	v_mov_b32_e32 v145, v169
	v_mov_b32_e32 v157, v171
	v_pk_mov_b32 v[146:147], v[162:163], v[158:159] op_sel:[1,0]
	v_mov_b32_e32 v163, v159
	v_pk_mov_b32 v[158:159], v[166:167], v[164:165] op_sel:[1,0]
	v_mov_b32_e32 v167, v165
	v_pk_fma_f32 v[160:161], v[54:55], v[54:55], v[168:169] op_sel_hi:[1,1,0]
	v_pk_fma_f32 v[164:165], v[56:57], v[56:57], v[170:171] op_sel_hi:[1,1,0]
	v_pk_mul_f32 v[168:169], v[48:49], v[48:49]
	v_pk_mul_f32 v[170:171], v[46:47], v[46:47]
	v_pk_add_f32 v[180:181], v[142:143], v[142:143] op_sel:[0,1] op_sel_hi:[1,0]
	v_pk_add_f32 v[182:183], v[140:141], v[140:141] op_sel:[0,1] op_sel_hi:[1,0]
	v_mul_f32_e32 v177, v52, v52
	v_pk_mul_f32 v[172:173], v[44:45], v[44:45]
	v_pk_mul_f32 v[174:175], v[42:43], v[42:43]
	v_mul_f32_e32 v176, v39, v39
	v_mul_f32_e32 v178, v41, v41
	v_pk_add_f32 v[156:157], v[144:145], v[156:157]
	v_pk_add_f32 v[140:141], v[146:147], v[162:163]
	v_pk_add_f32 v[142:143], v[158:159], v[166:167]
	v_pk_mov_b32 v[144:145], v[170:171], v[168:169] op_sel:[1,0]
	v_mov_b32_e32 v171, v169
	v_mov_b32_e32 v181, v155
	v_mov_b32_e32 v183, v179
	v_mul_f32_e32 v185, v50, v50
	v_mul_f32_e32 v190, v51, v51
	v_mul_f32_e32 v184, v53, v53
	v_mul_f32_e32 v193, v36, v36
	v_mul_f32_e32 v194, v37, v37
	v_pk_mov_b32 v[146:147], v[174:175], v[172:173] op_sel:[1,0]
	v_mov_b32_e32 v175, v173
	v_pk_fma_f32 v[158:159], v[38:39], v[38:39], v[176:177] op_sel_hi:[1,1,0]
	v_pk_fma_f32 v[162:163], v[40:41], v[40:41], v[178:179] op_sel_hi:[1,1,0]
	v_pk_add_f32 v[186:187], v[140:141], v[140:141] op_sel:[0,1] op_sel_hi:[1,0]
	v_pk_add_f32 v[188:189], v[142:143], v[142:143] op_sel:[0,1] op_sel_hi:[1,0]
	v_pk_add_f32 v[144:145], v[144:145], v[170:171]
	v_pk_add_f32 v[170:171], v[180:181], v[182:183]
	v_mov_b32_e32 v161, v177
	v_mov_b32_e32 v165, v184
	v_pk_mul_f32 v[166:167], v[32:33], v[32:33]
	v_pk_mul_f32 v[168:169], v[30:31], v[30:31]
	v_pk_mul_f32 v[172:173], v[28:29], v[28:29]
	v_pk_mul_f32 v[176:177], v[26:27], v[26:27]
	v_pk_add_f32 v[146:147], v[146:147], v[174:175]
	v_mov_b32_e32 v159, v193
	v_mov_b32_e32 v163, v194
	v_mov_b32_e32 v187, v185
	v_mov_b32_e32 v189, v190
	v_pk_add_f32 v[156:157], v[170:171], v[156:157]
	v_mul_f32_e32 v191, v34, v34
	v_mul_f32_e32 v192, v35, v35
	v_pk_add_f32 v[160:161], v[160:161], v[164:165]
	v_pk_mov_b32 v[164:165], v[168:169], v[166:167] op_sel:[1,0]
	v_mov_b32_e32 v169, v167
	v_pk_mov_b32 v[166:167], v[176:177], v[172:173] op_sel:[1,0]
	v_mov_b32_e32 v177, v173
	v_pk_add_f32 v[172:173], v[144:145], v[144:145] op_sel:[0,1] op_sel_hi:[1,0]
	v_pk_add_f32 v[174:175], v[146:147], v[146:147] op_sel:[0,1] op_sel_hi:[1,0]
	v_pk_add_f32 v[158:159], v[158:159], v[162:163]
	v_pk_add_f32 v[162:163], v[186:187], v[188:189]
	v_add_f32_e32 v155, v156, v157
	v_mov_b32_e32 v173, v191
	v_mov_b32_e32 v175, v192
	v_pk_add_f32 v[156:157], v[162:163], v[160:161]
	ds_bpermute_b32 v163, v1, v155
	v_pk_add_f32 v[160:161], v[172:173], v[174:175]
	v_add_f32_e32 v162, v156, v157
	v_pk_add_f32 v[156:157], v[160:161], v[158:159]
	ds_bpermute_b32 v158, v1, v162
	v_add_f32_e32 v156, v156, v157
	ds_bpermute_b32 v157, v1, v156
	s_waitcnt lgkmcnt(2)
	v_add_f32_e32 v155, v155, v163
	ds_bpermute_b32 v159, v148, v155
	s_waitcnt lgkmcnt(2)
	v_add_f32_e32 v158, v162, v158
	ds_bpermute_b32 v160, v148, v158
	s_waitcnt lgkmcnt(2)
	v_add_f32_e32 v156, v156, v157
	ds_bpermute_b32 v157, v148, v156
	s_waitcnt lgkmcnt(2)
	v_add_f32_e32 v155, v155, v159
	ds_bpermute_b32 v159, v149, v155
	s_waitcnt lgkmcnt(2)
	v_add_f32_e32 v158, v158, v160
	ds_bpermute_b32 v160, v149, v158
	s_waitcnt lgkmcnt(2)
	v_add_f32_e32 v156, v156, v157
	ds_bpermute_b32 v157, v149, v156
	s_waitcnt lgkmcnt(2)
	v_add_f32_e32 v155, v155, v159
	ds_bpermute_b32 v159, v150, v155
	s_waitcnt lgkmcnt(2)
	v_add_f32_e32 v158, v158, v160
	ds_bpermute_b32 v160, v150, v158
	s_waitcnt lgkmcnt(2)
	v_add_f32_e32 v156, v156, v157
	ds_bpermute_b32 v157, v150, v156
	s_waitcnt lgkmcnt(2)
	v_add_f32_e32 v155, v155, v159
	ds_bpermute_b32 v159, v151, v155
	s_waitcnt lgkmcnt(2)
	v_add_f32_e32 v158, v158, v160
	ds_bpermute_b32 v160, v151, v158
	s_waitcnt lgkmcnt(2)
	v_add_f32_e32 v156, v156, v157
	ds_bpermute_b32 v157, v151, v156
	s_waitcnt lgkmcnt(2)
	v_add_f32_e32 v155, v155, v159
	ds_bpermute_b32 v159, v152, v155
	s_waitcnt lgkmcnt(2)
	v_add_f32_e32 v158, v158, v160
	ds_bpermute_b32 v160, v152, v158
	s_waitcnt lgkmcnt(2)
	v_add_f32_e32 v156, v156, v157
	ds_bpermute_b32 v157, v152, v156
	s_waitcnt lgkmcnt(2)
	v_add_f32_e32 v155, v155, v159
	v_fmamk_f32 v155, v155, 0x3a800000, v153
	s_waitcnt lgkmcnt(1)
	v_add_f32_e32 v158, v158, v160
	v_mul_f32_e32 v159, 0x4f800000, v155
	v_cmp_gt_f32_e32 vcc, s17, v155
	v_fmamk_f32 v158, v158, 0x3a800000, v153
	s_waitcnt lgkmcnt(0)
	v_add_f32_e32 v156, v156, v157
	v_cndmask_b32_e32 v155, v155, v159, vcc
	v_mul_f32_e32 v157, 0x4f800000, v158
	v_cmp_gt_f32_e64 s[6:7], s17, v158
	v_sqrt_f32_e32 v159, v155
	v_fmamk_f32 v156, v156, 0x3a800000, v153
	v_cndmask_b32_e64 v157, v158, v157, s[6:7]
	v_mul_f32_e32 v158, 0x4f800000, v156
	v_cmp_gt_f32_e64 s[8:9], s17, v156
	v_sqrt_f32_e32 v160, v157
	v_add_u32_e32 v161, -1, v159
	v_cndmask_b32_e64 v156, v156, v158, s[8:9]
	v_sqrt_f32_e32 v158, v156
	v_add_u32_e32 v162, 1, v159
	v_fma_f32 v163, -v161, v159, v155
	v_pk_add_f32 v[144:145], v[164:165], v[168:169]
	v_fma_f32 v164, -v162, v159, v155
	v_add_u32_e32 v165, -1, v160
	v_cmp_ge_f32_e64 s[10:11], 0, v163
	v_pk_add_f32 v[146:147], v[166:167], v[176:177]
	v_add_u32_e32 v166, 1, v160
	v_cndmask_b32_e64 v159, v159, v161, s[10:11]
	v_fma_f32 v161, -v165, v160, v157
	v_cmp_lt_f32_e64 s[10:11], 0, v164
	v_fma_f32 v163, -v166, v160, v157
	v_add_u32_e32 v167, -1, v158
	v_cndmask_b32_e64 v159, v159, v162, s[10:11]
	v_cmp_ge_f32_e64 s[10:11], 0, v161
	v_add_u32_e32 v168, 1, v158
	v_fma_f32 v161, -v167, v158, v156
	v_cndmask_b32_e64 v160, v160, v165, s[10:11]
	v_cmp_lt_f32_e64 s[10:11], 0, v163
	v_fma_f32 v162, -v168, v158, v156
	v_mul_f32_e32 v163, 0x37800000, v159
	v_cndmask_b32_e64 v160, v160, v166, s[10:11]
	v_cmp_ge_f32_e64 s[10:11], 0, v161
	v_cndmask_b32_e32 v159, v159, v163, vcc
	v_cmp_class_f32_e32 vcc, v155, v154
	v_cndmask_b32_e64 v158, v158, v167, s[10:11]
	v_cmp_lt_f32_e64 s[10:11], 0, v162
	v_mul_f32_e32 v161, 0x37800000, v160
	v_cndmask_b32_e32 v155, v159, v155, vcc
	v_cndmask_b32_e64 v158, v158, v168, s[10:11]
	v_cndmask_b32_e64 v159, v160, v161, s[6:7]
	v_cmp_class_f32_e32 vcc, v157, v154
	v_mul_f32_e32 v160, 0x37800000, v158
	v_div_scale_f32 v161, s[6:7], v155, v155, 1.0
	v_cndmask_b32_e32 v157, v159, v157, vcc
	v_cndmask_b32_e64 v158, v158, v160, s[8:9]
	v_cmp_class_f32_e32 vcc, v156, v154
	v_rcp_f32_e32 v159, v161
	v_div_scale_f32 v160, s[8:9], v157, v157, 1.0
	v_cndmask_b32_e32 v158, v158, v156, vcc
	v_rcp_f32_e32 v164, v160
	v_div_scale_f32 v165, s[10:11], v158, v158, 1.0
	v_rcp_f32_e32 v167, v165
	v_fma_f32 v156, -v161, v159, 1.0
	v_div_scale_f32 v162, s[6:7], 1.0, v155, 1.0
	v_fmac_f32_e32 v159, v156, v159
	v_fma_f32 v156, -v160, v164, 1.0
	v_mul_f32_e32 v168, v162, v159
	v_div_scale_f32 v163, s[8:9], 1.0, v157, 1.0
	v_fmac_f32_e32 v164, v156, v164
	v_fma_f32 v156, -v165, v167, 1.0
	v_fma_f32 v169, -v161, v168, v162
	v_div_scale_f32 v166, s[10:11], 1.0, v158, 1.0
	v_mul_f32_e32 v170, v163, v164
	v_fmac_f32_e32 v167, v156, v167
	v_fmac_f32_e32 v168, v169, v159
	v_fma_f32 v156, -v160, v170, v163
	v_mul_f32_e32 v169, v166, v167
	v_fma_f32 v161, -v161, v168, v162
	s_mov_b64 vcc, s[6:7]
	v_fmac_f32_e32 v170, v156, v164
	v_fma_f32 v156, -v165, v169, v166
	v_div_fmas_f32 v159, v161, v159, v168
	v_fma_f32 v160, -v160, v170, v163
	v_fmac_f32_e32 v169, v156, v167
	v_div_fixup_f32 v156, v159, v155, 1.0
	s_mov_b64 vcc, s[8:9]
	v_div_fmas_f32 v155, v160, v164, v170
	v_fma_f32 v159, -v165, v169, v166
	v_pk_mul_f32 v[80:81], v[80:81], v[156:157] op_sel_hi:[1,0]
	v_pk_mul_f32 v[78:79], v[78:79], v[156:157] op_sel_hi:[1,0]
	s_mov_b64 vcc, s[10:11]
	v_pk_add_f32 v[88:89], v[88:89], 1.0 op_sel_hi:[1,0]
	v_pk_add_f32 v[86:87], v[86:87], 1.0 op_sel_hi:[1,0]
	v_pk_mul_f32 v[76:77], v[76:77], v[156:157] op_sel_hi:[1,0]
	v_pk_mul_f32 v[74:75], v[74:75], v[156:157] op_sel_hi:[1,0]
	v_pk_mul_f32 v[72:73], v[72:73], v[156:157] op_sel_hi:[1,0]
	v_pk_mul_f32 v[70:71], v[70:71], v[156:157] op_sel_hi:[1,0]
	v_pk_mul_f32 v[68:69], v[68:69], v[156:157] op_sel_hi:[1,0]
	v_pk_mul_f32 v[66:67], v[66:67], v[156:157] op_sel_hi:[1,0]
	v_div_fixup_f32 v156, v155, v157, 1.0
	v_div_fmas_f32 v155, v159, v167, v169
	v_pk_mul_f32 v[78:79], v[78:79], v[2:3]
	v_pk_mul_f32 v[80:81], v[80:81], v[4:5]
	v_pk_mul_f32 v[64:65], v[64:65], v[156:157] op_sel_hi:[1,0]
	v_pk_mul_f32 v[62:63], v[62:63], v[156:157] op_sel_hi:[1,0]
	v_pk_mul_f32 v[60:61], v[60:61], v[156:157] op_sel_hi:[1,0]
	v_pk_mul_f32 v[58:59], v[58:59], v[156:157] op_sel_hi:[1,0]
	v_pk_mul_f32 v[56:57], v[56:57], v[156:157] op_sel_hi:[1,0]
	v_pk_mul_f32 v[54:55], v[54:55], v[156:157] op_sel_hi:[1,0]
	v_pk_mul_f32 v[52:53], v[52:53], v[156:157] op_sel_hi:[1,0]
	v_pk_mul_f32 v[156:157], v[50:51], v[156:157] op_sel_hi:[1,0]
	v_div_fixup_f32 v50, v155, v158, 1.0
	v_pk_fma_f32 v[80:81], v[80:81], v[88:89], v[84:85]
	v_pk_fma_f32 v[78:79], v[78:79], v[86:87], v[82:83]
	v_pk_mul_f32 v[86:87], v[52:53], v[16:17]
	v_pk_mul_f32 v[48:49], v[48:49], v[50:51] op_sel_hi:[1,0]
	v_pk_mul_f32 v[46:47], v[46:47], v[50:51] op_sel_hi:[1,0]
	v_bfe_u32 v51, v78, 16, 1
	v_bfe_u32 v53, v80, 16, 1
	v_pk_mul_f32 v[82:83], v[54:55], v[10:11]
	v_pk_mul_f32 v[84:85], v[156:157], v[14:15]
	v_bfe_u32 v52, v79, 16, 1
	v_bfe_u32 v54, v81, 16, 1
	v_pk_mul_f32 v[88:89], v[46:47], v[2:3]
	v_pk_mul_f32 v[156:157], v[48:49], v[4:5]
	v_add3_u32 v46, v78, v51, s25
	v_add3_u32 v48, v80, v53, s25
	v_add3_u32 v47, v79, v52, s25
	v_add3_u32 v49, v81, v54, s25
	v_lshrrev_b32_e32 v46, 16, v46
	v_lshrrev_b32_e32 v48, 16, v48
	v_and_or_b32 v46, v47, s28, v46
	v_and_or_b32 v47, v49, s28, v48
	global_store_dwordx2 v[102:103], v[46:47], off
	global_load_dwordx4 v[46:49], v[134:135], off
	s_nop 0
	global_load_dwordx4 v[52:55], v[124:125], off offset:1024
	v_pk_mul_f32 v[74:75], v[74:75], v[6:7]
	v_pk_mul_f32 v[76:77], v[76:77], v[8:9]
	v_pk_mul_f32 v[70:71], v[70:71], v[10:11]
	v_pk_mul_f32 v[72:73], v[72:73], v[12:13]
	v_pk_mul_f32 v[66:67], v[66:67], v[14:15]
	v_pk_mul_f32 v[68:69], v[68:69], v[16:17]
	v_pk_mul_f32 v[62:63], v[62:63], v[2:3]
	v_pk_mul_f32 v[64:65], v[64:65], v[4:5]
	v_pk_mul_f32 v[58:59], v[58:59], v[6:7]
	v_pk_mul_f32 v[60:61], v[60:61], v[8:9]
	v_pk_mul_f32 v[56:57], v[56:57], v[12:13]
	v_mul_f32_e32 v178, v23, v23
	v_mul_f32_e32 v184, v25, v25
	v_mul_f32_e32 v195, v18, v18
	v_mul_f32_e32 v196, v19, v19
	v_mul_f32_e32 v197, v20, v20
	v_mul_f32_e32 v198, v21, v21
	v_pk_fma_f32 v[140:141], v[22:23], v[22:23], v[178:179] op_sel_hi:[1,1,0]
	v_pk_fma_f32 v[142:143], v[24:25], v[24:25], v[184:185] op_sel_hi:[1,1,0]
	v_mov_b32_e32 v141, v197
	v_mov_b32_e32 v143, v198
	v_lshl_add_u64 v[94:95], v[94:95], 0, s[38:39]
	s_cmp_lt_i32 s24, s5
	s_waitcnt vmcnt(0) lgkmcnt(0)
	v_pk_add_f32 v[48:49], v[48:49], 1.0 op_sel_hi:[1,0]
	v_pk_add_f32 v[46:47], v[46:47], 1.0 op_sel_hi:[1,0]
	v_pk_fma_f32 v[48:49], v[76:77], v[48:49], v[54:55]
	v_pk_fma_f32 v[46:47], v[74:75], v[46:47], v[52:53]
	v_bfe_u32 v53, v48, 16, 1
	v_bfe_u32 v51, v46, 16, 1
	v_bfe_u32 v52, v47, 16, 1
	v_bfe_u32 v54, v49, 16, 1
	v_add3_u32 v46, v46, v51, s25
	v_add3_u32 v48, v48, v53, s25
	v_add3_u32 v47, v47, v52, s25
	v_add3_u32 v49, v49, v54, s25
	v_lshrrev_b32_e32 v46, 16, v46
	v_lshrrev_b32_e32 v48, 16, v48
	v_and_or_b32 v46, v47, s28, v46
	v_and_or_b32 v47, v49, s28, v48
	global_store_dwordx2 v[102:103], v[46:47], off offset:512
	global_load_dwordx4 v[46:49], v[130:131], off
	s_nop 0
	global_load_dwordx4 v[52:55], v[124:125], off offset:2048
	s_waitcnt vmcnt(0) lgkmcnt(0)
	v_pk_add_f32 v[48:49], v[48:49], 1.0 op_sel_hi:[1,0]
	v_pk_add_f32 v[46:47], v[46:47], 1.0 op_sel_hi:[1,0]
	v_pk_fma_f32 v[48:49], v[72:73], v[48:49], v[54:55]
	v_pk_fma_f32 v[46:47], v[70:71], v[46:47], v[52:53]
	v_bfe_u32 v53, v48, 16, 1
	v_bfe_u32 v51, v46, 16, 1
	v_bfe_u32 v52, v47, 16, 1
	v_bfe_u32 v54, v49, 16, 1
	v_add3_u32 v46, v46, v51, s25
	v_add3_u32 v48, v48, v53, s25
	v_add3_u32 v47, v47, v52, s25
	v_add3_u32 v49, v49, v54, s25
	v_lshrrev_b32_e32 v46, 16, v46
	v_lshrrev_b32_e32 v48, 16, v48
	v_and_or_b32 v46, v47, s28, v46
	v_and_or_b32 v47, v49, s28, v48
	global_store_dwordx2 v[102:103], v[46:47], off offset:1024
	global_load_dwordx4 v[46:49], v[128:129], off
	s_nop 0
	global_load_dwordx4 v[52:55], v[124:125], off offset:3072
	s_waitcnt vmcnt(0) lgkmcnt(0)
	v_pk_add_f32 v[48:49], v[48:49], 1.0 op_sel_hi:[1,0]
	v_pk_add_f32 v[46:47], v[46:47], 1.0 op_sel_hi:[1,0]
	v_pk_fma_f32 v[48:49], v[68:69], v[48:49], v[54:55]
	v_pk_fma_f32 v[46:47], v[66:67], v[46:47], v[52:53]
	v_bfe_u32 v53, v48, 16, 1
	v_bfe_u32 v51, v46, 16, 1
	v_bfe_u32 v52, v47, 16, 1
	v_bfe_u32 v54, v49, 16, 1
	v_add3_u32 v46, v46, v51, s25
	v_add3_u32 v48, v48, v53, s25
	v_add3_u32 v47, v47, v52, s25
	v_add3_u32 v49, v49, v54, s25
	v_lshrrev_b32_e32 v46, 16, v46
	v_lshrrev_b32_e32 v48, 16, v48
	v_and_or_b32 v46, v47, s28, v46
	v_and_or_b32 v47, v49, s28, v48
	global_store_dwordx2 v[102:103], v[46:47], off offset:1536
	global_load_dwordx4 v[46:49], v[126:127], off
	s_nop 0
	global_load_dwordx4 v[52:55], v[110:111], off
	s_waitcnt vmcnt(0) lgkmcnt(0)
	v_pk_add_f32 v[48:49], v[48:49], 1.0 op_sel_hi:[1,0]
	v_pk_add_f32 v[46:47], v[46:47], 1.0 op_sel_hi:[1,0]
	v_pk_fma_f32 v[48:49], v[64:65], v[48:49], v[54:55]
	v_pk_fma_f32 v[46:47], v[62:63], v[46:47], v[52:53]
	v_bfe_u32 v53, v48, 16, 1
	v_bfe_u32 v51, v46, 16, 1
	v_bfe_u32 v52, v47, 16, 1
	v_bfe_u32 v54, v49, 16, 1
	v_add3_u32 v46, v46, v51, s25
	v_add3_u32 v48, v48, v53, s25
	v_add3_u32 v47, v47, v52, s25
	v_add3_u32 v49, v49, v54, s25
	v_lshrrev_b32_e32 v46, 16, v46
	v_lshrrev_b32_e32 v48, 16, v48
	v_and_or_b32 v46, v47, s28, v46
	v_and_or_b32 v47, v49, s28, v48
	global_store_dwordx2 v[102:103], v[46:47], off offset:2048
	global_load_dwordx4 v[46:49], v[120:121], off
	s_nop 0
	global_load_dwordx4 v[52:55], v[110:111], off offset:1024
	s_waitcnt vmcnt(0) lgkmcnt(0)
	v_pk_add_f32 v[48:49], v[48:49], 1.0 op_sel_hi:[1,0]
	v_pk_add_f32 v[46:47], v[46:47], 1.0 op_sel_hi:[1,0]
	v_pk_fma_f32 v[48:49], v[60:61], v[48:49], v[54:55]
	v_pk_fma_f32 v[46:47], v[58:59], v[46:47], v[52:53]
	v_bfe_u32 v53, v48, 16, 1
	v_bfe_u32 v51, v46, 16, 1
	v_bfe_u32 v52, v47, 16, 1
	v_bfe_u32 v54, v49, 16, 1
	v_add3_u32 v46, v46, v51, s25
	v_add3_u32 v48, v48, v53, s25
	v_add3_u32 v47, v47, v52, s25
	v_add3_u32 v49, v49, v54, s25
	v_lshrrev_b32_e32 v46, 16, v46
	v_lshrrev_b32_e32 v48, 16, v48
	v_and_or_b32 v46, v47, s28, v46
	v_and_or_b32 v47, v49, s28, v48
	global_store_dwordx2 v[102:103], v[46:47], off offset:2560
	global_load_dwordx4 v[46:49], v[116:117], off
	s_nop 0
	global_load_dwordx4 v[52:55], v[110:111], off offset:2048
	v_pk_add_f32 v[58:59], v[146:147], v[146:147] op_sel:[0,1] op_sel_hi:[1,0]
	v_pk_add_f32 v[60:61], v[140:141], v[142:143]
	v_mov_b32_e32 v59, v196
	s_waitcnt vmcnt(0) lgkmcnt(0)
	v_pk_add_f32 v[48:49], v[48:49], 1.0 op_sel_hi:[1,0]
	v_pk_add_f32 v[46:47], v[46:47], 1.0 op_sel_hi:[1,0]
	v_pk_fma_f32 v[48:49], v[56:57], v[48:49], v[54:55]
	v_pk_fma_f32 v[46:47], v[82:83], v[46:47], v[52:53]
	v_bfe_u32 v53, v48, 16, 1
	v_bfe_u32 v51, v46, 16, 1
	v_bfe_u32 v52, v47, 16, 1
	v_bfe_u32 v54, v49, 16, 1
	v_add3_u32 v46, v46, v51, s25
	v_add3_u32 v48, v48, v53, s25
	v_add3_u32 v47, v47, v52, s25
	v_add3_u32 v49, v49, v54, s25
	v_lshrrev_b32_e32 v46, 16, v46
	v_lshrrev_b32_e32 v48, 16, v48
	v_and_or_b32 v46, v47, s28, v46
	v_and_or_b32 v47, v49, s28, v48
	global_store_dwordx2 v[102:103], v[46:47], off offset:3072
	global_load_dwordx4 v[46:49], v[112:113], off
	s_nop 0
	global_load_dwordx4 v[52:55], v[110:111], off offset:3072
	v_pk_add_f32 v[56:57], v[144:145], v[144:145] op_sel:[0,1] op_sel_hi:[1,0]
	s_waitcnt vmcnt(0) lgkmcnt(0)
	v_pk_add_f32 v[48:49], v[48:49], 1.0 op_sel_hi:[1,0]
	v_pk_add_f32 v[46:47], v[46:47], 1.0 op_sel_hi:[1,0]
	v_pk_fma_f32 v[48:49], v[86:87], v[48:49], v[54:55]
	v_pk_fma_f32 v[46:47], v[84:85], v[46:47], v[52:53]
	v_bfe_u32 v53, v48, 16, 1
	v_bfe_u32 v51, v46, 16, 1
	v_bfe_u32 v52, v47, 16, 1
	v_bfe_u32 v54, v49, 16, 1
	v_add3_u32 v46, v46, v51, s25
	v_add3_u32 v48, v48, v53, s25
	v_add3_u32 v47, v47, v52, s25
	v_add3_u32 v49, v49, v54, s25
	v_lshrrev_b32_e32 v46, 16, v46
	v_lshrrev_b32_e32 v48, 16, v48
	v_and_or_b32 v46, v47, s28, v46
	v_and_or_b32 v47, v49, s28, v48
	global_store_dwordx2 v[102:103], v[46:47], off offset:3584
	global_load_dwordx4 v[46:49], v[138:139], off
	s_nop 0
	global_load_dwordx4 v[52:55], v[108:109], off
	v_mov_b32_e32 v57, v195
	s_waitcnt vmcnt(0) lgkmcnt(0)
	v_pk_add_f32 v[48:49], v[48:49], 1.0 op_sel_hi:[1,0]
	v_pk_add_f32 v[46:47], v[46:47], 1.0 op_sel_hi:[1,0]
	v_pk_fma_f32 v[48:49], v[156:157], v[48:49], v[54:55]
	v_pk_fma_f32 v[46:47], v[88:89], v[46:47], v[52:53]
	v_bfe_u32 v53, v48, 16, 1
	v_bfe_u32 v51, v46, 16, 1
	v_bfe_u32 v52, v47, 16, 1
	v_bfe_u32 v54, v49, 16, 1
	v_add3_u32 v46, v46, v51, s25
	v_add3_u32 v48, v48, v53, s25
	v_add3_u32 v47, v47, v52, s25
	v_add3_u32 v49, v49, v54, s25
	v_lshrrev_b32_e32 v46, 16, v46
	v_lshrrev_b32_e32 v48, 16, v48
	v_and_or_b32 v46, v47, s28, v46
	v_and_or_b32 v47, v49, s28, v48
	global_store_dwordx2 v[104:105], v[46:47], off
	global_load_dwordx4 v[46:49], v[136:137], off
	s_nop 0
	global_load_dwordx4 v[52:55], v[108:109], off offset:1024
	v_pk_mul_f32 v[44:45], v[44:45], v[50:51] op_sel_hi:[1,0]
	v_pk_mul_f32 v[42:43], v[42:43], v[50:51] op_sel_hi:[1,0]
	v_pk_mul_f32 v[44:45], v[44:45], v[8:9]
	v_pk_mul_f32 v[42:43], v[42:43], v[6:7]
	s_waitcnt vmcnt(0) lgkmcnt(0)
	v_pk_add_f32 v[48:49], v[48:49], 1.0 op_sel_hi:[1,0]
	v_pk_add_f32 v[46:47], v[46:47], 1.0 op_sel_hi:[1,0]
	v_pk_fma_f32 v[44:45], v[44:45], v[48:49], v[54:55]
	v_pk_fma_f32 v[42:43], v[42:43], v[46:47], v[52:53]
	v_bfe_u32 v48, v44, 16, 1
	v_bfe_u32 v46, v42, 16, 1
	v_bfe_u32 v47, v43, 16, 1
	v_bfe_u32 v49, v45, 16, 1
	v_add3_u32 v42, v42, v46, s25
	v_add3_u32 v44, v44, v48, s25
	v_add3_u32 v43, v43, v47, s25
	v_add3_u32 v45, v45, v49, s25
	v_lshrrev_b32_e32 v42, 16, v42
	v_lshrrev_b32_e32 v44, 16, v44
	v_and_or_b32 v42, v43, s28, v42
	v_and_or_b32 v43, v45, s28, v44
	global_store_dwordx2 v[104:105], v[42:43], off offset:512
	global_load_dwordx4 v[42:45], v[132:133], off
	s_nop 0
	global_load_dwordx4 v[46:49], v[108:109], off offset:2048
	v_pk_add_f32 v[52:53], v[56:57], v[58:59]
	s_waitcnt vmcnt(0) lgkmcnt(0)
	v_pk_add_f32 v[44:45], v[44:45], 1.0 op_sel_hi:[1,0]
	v_pk_add_f32 v[52:53], v[52:53], v[60:61]
	v_pk_add_f32 v[42:43], v[42:43], 1.0 op_sel_hi:[1,0]
	v_add_f32_e32 v51, v52, v53
	ds_bpermute_b32 v52, v1, v51
	s_waitcnt lgkmcnt(0)
	v_add_f32_e32 v51, v51, v52
	ds_bpermute_b32 v52, v148, v51
	s_waitcnt lgkmcnt(0)
	v_add_f32_e32 v51, v51, v52
	v_pk_mul_f32 v[40:41], v[40:41], v[50:51] op_sel_hi:[1,0]
	v_pk_mul_f32 v[38:39], v[38:39], v[50:51] op_sel_hi:[1,0]
	v_pk_mul_f32 v[40:41], v[40:41], v[12:13]
	v_pk_mul_f32 v[38:39], v[38:39], v[10:11]
	v_pk_fma_f32 v[40:41], v[40:41], v[44:45], v[48:49]
	v_pk_fma_f32 v[38:39], v[38:39], v[42:43], v[46:47]
	v_bfe_u32 v44, v40, 16, 1
	v_bfe_u32 v42, v38, 16, 1
	v_bfe_u32 v43, v39, 16, 1
	v_bfe_u32 v45, v41, 16, 1
	v_add3_u32 v38, v38, v42, s25
	v_add3_u32 v40, v40, v44, s25
	v_add3_u32 v39, v39, v43, s25
	v_add3_u32 v41, v41, v45, s25
	v_lshrrev_b32_e32 v38, 16, v38
	v_lshrrev_b32_e32 v40, 16, v40
	v_and_or_b32 v38, v39, s28, v38
	v_and_or_b32 v39, v41, s28, v40
	global_store_dwordx2 v[104:105], v[38:39], off offset:1024
	global_load_dwordx4 v[38:41], v[122:123], off
	s_nop 0
	global_load_dwordx4 v[42:45], v[108:109], off offset:3072
	v_pk_mul_f32 v[36:37], v[36:37], v[50:51] op_sel_hi:[1,0]
	v_pk_mul_f32 v[34:35], v[34:35], v[50:51] op_sel_hi:[1,0]
	v_pk_mul_f32 v[36:37], v[36:37], v[16:17]
	v_pk_mul_f32 v[34:35], v[34:35], v[14:15]
	ds_bpermute_b32 v46, v149, v51
	s_waitcnt lgkmcnt(0)
	v_add_f32_e32 v46, v51, v46
	ds_bpermute_b32 v47, v150, v46
	s_waitcnt lgkmcnt(0)
	v_add_f32_e32 v46, v46, v47
	ds_bpermute_b32 v47, v151, v46
	s_waitcnt lgkmcnt(0)
	v_add_f32_e32 v46, v46, v47
	ds_bpermute_b32 v47, v152, v46
	s_waitcnt lgkmcnt(0)
	v_add_f32_e32 v46, v46, v47
	v_fmamk_f32 v46, v46, 0x3a800000, v153
	v_mul_f32_e32 v47, 0x4f800000, v46
	v_cmp_gt_f32_e32 vcc, s17, v46
	s_waitcnt vmcnt(0)
	v_pk_add_f32 v[40:41], v[40:41], 1.0 op_sel_hi:[1,0]
	v_pk_add_f32 v[38:39], v[38:39], 1.0 op_sel_hi:[1,0]
	v_pk_fma_f32 v[36:37], v[36:37], v[40:41], v[44:45]
	v_pk_fma_f32 v[34:35], v[34:35], v[38:39], v[42:43]
	v_bfe_u32 v40, v36, 16, 1
	v_bfe_u32 v38, v34, 16, 1
	v_bfe_u32 v39, v35, 16, 1
	v_bfe_u32 v41, v37, 16, 1
	v_add3_u32 v34, v34, v38, s25
	v_add3_u32 v36, v36, v40, s25
	v_add3_u32 v35, v35, v39, s25
	v_add3_u32 v37, v37, v41, s25
	v_lshrrev_b32_e32 v34, 16, v34
	v_lshrrev_b32_e32 v36, 16, v36
	v_and_or_b32 v34, v35, s28, v34
	v_and_or_b32 v35, v37, s28, v36
	global_store_dwordx2 v[104:105], v[34:35], off offset:1536
	global_load_dwordx4 v[34:37], v[118:119], off
	s_nop 0
	global_load_dwordx4 v[38:41], v[106:107], off
	v_cndmask_b32_e32 v42, v46, v47, vcc
	v_sqrt_f32_e32 v43, v42
	s_waitcnt vmcnt(0) lgkmcnt(0)
	v_pk_add_f32 v[36:37], v[36:37], 1.0 op_sel_hi:[1,0]
	v_add_u32_e32 v44, -1, v43
	v_add_u32_e32 v45, 1, v43
	v_fma_f32 v46, -v44, v43, v42
	v_fma_f32 v47, -v45, v43, v42
	v_cmp_ge_f32_e64 s[6:7], 0, v46
	v_pk_add_f32 v[34:35], v[34:35], 1.0 op_sel_hi:[1,0]
	s_nop 0
	v_cndmask_b32_e64 v43, v43, v44, s[6:7]
	v_cmp_lt_f32_e64 s[6:7], 0, v47
	s_nop 1
	v_cndmask_b32_e64 v43, v43, v45, s[6:7]
	v_mul_f32_e32 v44, 0x37800000, v43
	v_cndmask_b32_e32 v43, v43, v44, vcc
	v_cmp_class_f32_e32 vcc, v42, v154
	s_nop 1
	v_cndmask_b32_e32 v42, v43, v42, vcc
	v_div_scale_f32 v43, s[6:7], v42, v42, 1.0
	v_rcp_f32_e32 v45, v43
	v_div_scale_f32 v44, vcc, 1.0, v42, 1.0
	v_fma_f32 v46, -v43, v45, 1.0
	v_fmac_f32_e32 v45, v46, v45
	v_mul_f32_e32 v46, v44, v45
	v_fma_f32 v47, -v43, v46, v44
	v_fmac_f32_e32 v46, v47, v45
	v_fma_f32 v43, -v43, v46, v44
	v_div_fmas_f32 v43, v43, v45, v46
	v_div_fixup_f32 v42, v43, v42, 1.0
	v_pk_mul_f32 v[32:33], v[32:33], v[42:43] op_sel_hi:[1,0]
	v_pk_mul_f32 v[30:31], v[30:31], v[42:43] op_sel_hi:[1,0]
	v_pk_mul_f32 v[32:33], v[32:33], v[4:5]
	v_pk_mul_f32 v[30:31], v[30:31], v[2:3]
	v_pk_fma_f32 v[32:33], v[32:33], v[36:37], v[40:41]
	v_pk_fma_f32 v[30:31], v[30:31], v[34:35], v[38:39]
	v_bfe_u32 v36, v32, 16, 1
	v_bfe_u32 v34, v30, 16, 1
	v_bfe_u32 v35, v31, 16, 1
	v_bfe_u32 v37, v33, 16, 1
	v_add3_u32 v30, v30, v34, s25
	v_add3_u32 v32, v32, v36, s25
	v_add3_u32 v31, v31, v35, s25
	v_add3_u32 v33, v33, v37, s25
	v_lshrrev_b32_e32 v30, 16, v30
	v_lshrrev_b32_e32 v32, 16, v32
	v_and_or_b32 v30, v31, s28, v30
	v_and_or_b32 v31, v33, s28, v32
	global_store_dwordx2 v[104:105], v[30:31], off offset:2048
	global_load_dwordx4 v[30:33], v[114:115], off
	s_nop 0
	global_load_dwordx4 v[34:37], v[106:107], off offset:1024
	v_pk_mul_f32 v[28:29], v[28:29], v[42:43] op_sel_hi:[1,0]
	v_pk_mul_f32 v[26:27], v[26:27], v[42:43] op_sel_hi:[1,0]
	v_pk_mul_f32 v[28:29], v[28:29], v[8:9]
	v_pk_mul_f32 v[26:27], v[26:27], v[6:7]
	v_lshl_add_u64 v[38:39], s[40:41], 0, v[98:99]
	v_pk_mul_f32 v[24:25], v[24:25], v[42:43] op_sel_hi:[1,0]
	v_pk_mul_f32 v[22:23], v[22:23], v[42:43] op_sel_hi:[1,0]
	v_pk_mul_f32 v[24:25], v[24:25], v[12:13]
	v_pk_mul_f32 v[22:23], v[22:23], v[10:11]
	v_pk_mul_f32 v[20:21], v[20:21], v[42:43] op_sel_hi:[1,0]
	v_pk_mul_f32 v[18:19], v[18:19], v[42:43] op_sel_hi:[1,0]
	v_pk_mul_f32 v[20:21], v[20:21], v[16:17]
	v_pk_mul_f32 v[18:19], v[18:19], v[14:15]
	s_waitcnt vmcnt(0) lgkmcnt(0)
	v_pk_add_f32 v[32:33], v[32:33], 1.0 op_sel_hi:[1,0]
	v_pk_add_f32 v[30:31], v[30:31], 1.0 op_sel_hi:[1,0]
	v_pk_fma_f32 v[28:29], v[28:29], v[32:33], v[36:37]
	v_pk_fma_f32 v[26:27], v[26:27], v[30:31], v[34:35]
	v_bfe_u32 v32, v28, 16, 1
	v_bfe_u32 v30, v26, 16, 1
	v_bfe_u32 v31, v27, 16, 1
	v_bfe_u32 v33, v29, 16, 1
	v_add3_u32 v26, v26, v30, s25
	v_add3_u32 v28, v28, v32, s25
	v_add3_u32 v27, v27, v31, s25
	v_add3_u32 v29, v29, v33, s25
	v_lshrrev_b32_e32 v26, 16, v26
	v_lshrrev_b32_e32 v28, 16, v28
	v_and_or_b32 v26, v27, s28, v26
	v_and_or_b32 v27, v29, s28, v28
	global_store_dwordx2 v[104:105], v[26:27], off offset:2560
	global_load_dwordx4 v[26:29], v[38:39], off
	s_nop 0
	global_load_dwordx4 v[30:33], v[106:107], off offset:2048
	v_lshl_add_u64 v[34:35], s[40:41], 0, v[100:101]
	s_waitcnt vmcnt(0) lgkmcnt(0)
	v_pk_add_f32 v[28:29], v[28:29], 1.0 op_sel_hi:[1,0]
	v_pk_add_f32 v[26:27], v[26:27], 1.0 op_sel_hi:[1,0]
	v_pk_fma_f32 v[24:25], v[24:25], v[28:29], v[32:33]
	v_pk_fma_f32 v[22:23], v[22:23], v[26:27], v[30:31]
	v_bfe_u32 v28, v24, 16, 1
	v_bfe_u32 v26, v22, 16, 1
	v_bfe_u32 v27, v23, 16, 1
	v_bfe_u32 v29, v25, 16, 1
	v_add3_u32 v22, v22, v26, s25
	v_add3_u32 v24, v24, v28, s25
	v_add3_u32 v23, v23, v27, s25
	v_add3_u32 v25, v25, v29, s25
	v_lshrrev_b32_e32 v22, 16, v22
	v_lshrrev_b32_e32 v24, 16, v24
	v_and_or_b32 v22, v23, s28, v22
	v_and_or_b32 v23, v25, s28, v24
	global_store_dwordx2 v[104:105], v[22:23], off offset:3072
	global_load_dwordx4 v[22:25], v[34:35], off
	s_nop 0
	global_load_dwordx4 v[26:29], v[106:107], off offset:3072
	s_waitcnt vmcnt(0) lgkmcnt(0)
	v_pk_add_f32 v[24:25], v[24:25], 1.0 op_sel_hi:[1,0]
	v_pk_add_f32 v[22:23], v[22:23], 1.0 op_sel_hi:[1,0]
	v_pk_fma_f32 v[20:21], v[20:21], v[24:25], v[28:29]
	v_pk_fma_f32 v[18:19], v[18:19], v[22:23], v[26:27]
	v_bfe_u32 v24, v20, 16, 1
	v_bfe_u32 v22, v18, 16, 1
	v_bfe_u32 v23, v19, 16, 1
	v_bfe_u32 v25, v21, 16, 1
	v_add3_u32 v18, v18, v22, s25
	v_add3_u32 v20, v20, v24, s25
	v_add3_u32 v19, v19, v23, s25
	v_add3_u32 v21, v21, v25, s25
	v_lshrrev_b32_e32 v18, 16, v18
	v_lshrrev_b32_e32 v20, 16, v20
	v_and_or_b32 v18, v19, s28, v18
	v_and_or_b32 v19, v21, s28, v20
	global_store_dwordx2 v[104:105], v[18:19], off offset:3584
	s_cbranch_scc1 .LBB0_3194

.LBB0_3215:
	v_mul_f32_e32 v148, 0xbfb8aa3b, v126
	v_exp_f32_e32 v149, v148
	v_lshl_add_u32 v148, s48, 8, v1
	v_lshl_or_b32 v150, s49, 7, v142
	v_mul_f32_e32 v156, 0xbfb8aa3b, v127
	v_add_f32_e32 v149, 1.0, v149
	v_div_scale_f32 v152, s[48:49], v149, v149, v126
	v_rcp_f32_e32 v153, v152
	v_div_scale_f32 v154, vcc, v126, v149, v126
	v_exp_f32_e32 v156, v156
	v_fma_f32 v155, -v152, v153, 1.0
	v_fmac_f32_e32 v153, v155, v153
	v_mul_f32_e32 v155, v154, v153
	v_fma_f32 v157, -v152, v155, v154
	v_fmac_f32_e32 v155, v157, v153
	v_fma_f32 v152, -v152, v155, v154
	v_add_f32_e32 v154, 1.0, v156
	v_div_scale_f32 v156, s[48:49], v154, v154, v127
	v_rcp_f32_e32 v157, v156
	v_div_fmas_f32 v152, v152, v153, v155
	v_div_fixup_f32 v126, v152, v149, v126
	v_mul_f32_e32 v122, v126, v122
	v_fma_f32 v126, -v156, v157, 1.0
	v_fmac_f32_e32 v157, v126, v157
	v_div_scale_f32 v126, vcc, v127, v154, v127
	v_mul_f32_e32 v149, v126, v157
	v_fma_f32 v152, -v156, v149, v126
	v_fmac_f32_e32 v149, v152, v157
	v_mul_f32_e32 v152, 0xbfb8aa3b, v128
	v_exp_f32_e32 v152, v152
	v_fma_f32 v126, -v156, v149, v126
	v_div_fmas_f32 v126, v126, v157, v149
	v_div_fixup_f32 v126, v126, v154, v127
	v_add_f32_e32 v149, 1.0, v152
	v_div_scale_f32 v152, s[48:49], v149, v149, v128
	v_rcp_f32_e32 v153, v152
	v_mul_f32_e32 v123, v126, v123
	v_mul_f32_e32 v127, 0xbfb8aa3b, v129
	v_cvt_pk_bf16_f32 v122, v122, v123
	v_fma_f32 v123, -v152, v153, 1.0
	v_exp_f32_e32 v127, v127
	v_fmac_f32_e32 v153, v123, v153
	v_div_scale_f32 v123, vcc, v128, v149, v128
	v_mul_f32_e32 v126, v123, v153
	v_fma_f32 v154, -v152, v126, v123
	v_fmac_f32_e32 v126, v154, v153
	v_add_f32_e32 v127, 1.0, v127
	v_fma_f32 v123, -v152, v126, v123
	v_div_scale_f32 v152, s[48:49], v127, v127, v129
	v_rcp_f32_e32 v154, v152
	v_div_fmas_f32 v123, v123, v153, v126
	v_div_fixup_f32 v123, v123, v149, v128
	v_mul_f32_e32 v123, v123, v124
	v_fma_f32 v124, -v152, v154, 1.0
	v_fmac_f32_e32 v154, v124, v154
	v_div_scale_f32 v124, vcc, v129, v127, v129
	v_mul_f32_e32 v126, v124, v154
	v_fma_f32 v128, -v152, v126, v124
	v_fmac_f32_e32 v126, v128, v154
	v_mul_f32_e32 v128, 0xbfb8aa3b, v118
	v_exp_f32_e32 v128, v128
	v_fma_f32 v124, -v152, v126, v124
	v_div_fmas_f32 v124, v124, v154, v126
	v_div_fixup_f32 v124, v124, v127, v129
	v_add_f32_e32 v126, 1.0, v128
	v_div_scale_f32 v128, s[48:49], v126, v126, v118
	v_rcp_f32_e32 v149, v128
	v_mul_f32_e32 v124, v124, v125
	v_mul_f32_e32 v127, 0xbfb8aa3b, v119
	v_cvt_pk_bf16_f32 v123, v123, v124
	v_fma_f32 v124, -v128, v149, 1.0
	v_exp_f32_e32 v127, v127
	v_fmac_f32_e32 v149, v124, v149
	v_div_scale_f32 v124, vcc, v118, v126, v118
	v_mul_f32_e32 v125, v124, v149
	v_fma_f32 v129, -v128, v125, v124
	v_fmac_f32_e32 v125, v129, v149
	v_add_f32_e32 v127, 1.0, v127
	v_fma_f32 v124, -v128, v125, v124
	v_div_scale_f32 v128, s[48:49], v127, v127, v119
	v_rcp_f32_e32 v129, v128
	v_div_fmas_f32 v124, v124, v149, v125
	v_div_fixup_f32 v118, v124, v126, v118
	v_mul_f32_e32 v114, v118, v114
	v_fma_f32 v118, -v128, v129, 1.0
	v_fmac_f32_e32 v129, v118, v129
	v_div_scale_f32 v118, vcc, v119, v127, v119
	v_mul_f32_e32 v124, v118, v129
	v_fma_f32 v125, -v128, v124, v118
	v_fmac_f32_e32 v124, v125, v129
	v_mul_f32_e32 v125, 0xbfb8aa3b, v120
	v_exp_f32_e32 v125, v125
	v_fma_f32 v118, -v128, v124, v118
	v_div_fmas_f32 v118, v118, v129, v124
	v_div_fixup_f32 v118, v118, v127, v119
	v_add_f32_e32 v125, 1.0, v125
	v_div_scale_f32 v126, s[48:49], v125, v125, v120
	v_rcp_f32_e32 v128, v126
	v_mul_f32_e32 v115, v118, v115
	v_mul_f32_e32 v118, 0xbfb8aa3b, v121
	v_exp_f32_e32 v118, v118
	v_cvt_pk_bf16_f32 v124, v114, v115
	v_fma_f32 v114, -v126, v128, 1.0
	v_fmac_f32_e32 v128, v114, v128
	v_div_scale_f32 v114, vcc, v120, v125, v120
	v_mul_f32_e32 v115, v114, v128
	v_fma_f32 v119, -v126, v115, v114
	v_add_f32_e32 v118, 1.0, v118
	v_fmac_f32_e32 v115, v119, v128
	v_div_scale_f32 v119, s[48:49], v118, v118, v121
	v_fma_f32 v114, -v126, v115, v114
	v_rcp_f32_e32 v126, v119
	v_div_fmas_f32 v114, v114, v128, v115
	v_div_fixup_f32 v114, v114, v125, v120
	v_mul_f32_e32 v114, v114, v116
	v_fma_f32 v115, -v119, v126, 1.0
	v_fmac_f32_e32 v126, v115, v126
	v_div_scale_f32 v115, vcc, v121, v118, v121
	v_mul_f32_e32 v116, v115, v126
	v_fma_f32 v120, -v119, v116, v115
	v_fmac_f32_e32 v116, v120, v126
	v_fma_f32 v115, -v119, v116, v115
	v_div_fmas_f32 v115, v115, v126, v116
	v_div_fixup_f32 v115, v115, v118, v121
	v_mul_f32_e32 v115, v115, v117
	v_cvt_pk_bf16_f32 v125, v114, v115
	v_mul_f32_e32 v114, 0xbfb8aa3b, v110
	v_exp_f32_e32 v116, v114
	v_ashrrev_i32_e32 v151, 31, v150
	v_mov_b64_e32 v[114:115], s[22:23]
	v_mad_i64_i32 v[118:119], s[48:49], v148, s64, v[114:115]
	v_add_f32_e32 v120, 1.0, v116
	v_div_scale_f32 v121, s[48:49], v120, v120, v110
	v_rcp_f32_e32 v126, v121
	v_lshlrev_b64 v[116:117], 1, v[150:151]
	v_lshl_add_u64 v[118:119], v[118:119], 0, v[116:117]
	global_store_dwordx4 v[118:119], v[122:125], off
	v_fma_f32 v118, -v121, v126, 1.0
	v_fmac_f32_e32 v126, v118, v126
	v_mul_f32_e32 v122, 0xbfb8aa3b, v111
	v_div_scale_f32 v118, vcc, v110, v120, v110
	v_exp_f32_e32 v122, v122
	v_mul_f32_e32 v119, v118, v126
	v_fma_f32 v123, -v121, v119, v118
	v_fmac_f32_e32 v119, v123, v126
	v_fma_f32 v118, -v121, v119, v118
	v_add_f32_e32 v121, 1.0, v122
	v_div_scale_f32 v122, s[48:49], v121, v121, v111
	v_rcp_f32_e32 v123, v122
	v_div_fmas_f32 v118, v118, v126, v119
	v_div_fixup_f32 v110, v118, v120, v110
	v_mul_f32_e32 v106, v110, v106
	v_fma_f32 v110, -v122, v123, 1.0
	v_fmac_f32_e32 v123, v110, v123
	v_div_scale_f32 v110, vcc, v111, v121, v111
	v_mul_f32_e32 v118, v110, v123
	v_fma_f32 v119, -v122, v118, v110
	v_fmac_f32_e32 v118, v119, v123
	v_mul_f32_e32 v119, 0xbfb8aa3b, v112
	v_exp_f32_e32 v119, v119
	v_fma_f32 v110, -v122, v118, v110
	v_div_fmas_f32 v110, v110, v123, v118
	v_div_fixup_f32 v110, v110, v121, v111
	v_add_f32_e32 v118, 1.0, v119
	v_div_scale_f32 v119, s[48:49], v118, v118, v112
	v_rcp_f32_e32 v120, v119
	v_mul_f32_e32 v107, v110, v107
	v_mul_f32_e32 v111, 0xbfb8aa3b, v113
	v_cvt_pk_bf16_f32 v106, v106, v107
	v_fma_f32 v107, -v119, v120, 1.0
	v_exp_f32_e32 v111, v111
	v_fmac_f32_e32 v120, v107, v120
	v_div_scale_f32 v107, vcc, v112, v118, v112
	v_mul_f32_e32 v110, v107, v120
	v_fma_f32 v121, -v119, v110, v107
	v_fmac_f32_e32 v110, v121, v120
	v_add_f32_e32 v111, 1.0, v111
	v_fma_f32 v107, -v119, v110, v107
	v_div_scale_f32 v119, s[48:49], v111, v111, v113
	v_rcp_f32_e32 v121, v119
	v_div_fmas_f32 v107, v107, v120, v110
	v_div_fixup_f32 v107, v107, v118, v112
	v_mul_f32_e32 v107, v107, v108
	v_fma_f32 v108, -v119, v121, 1.0
	v_fmac_f32_e32 v121, v108, v121
	v_div_scale_f32 v108, vcc, v113, v111, v113
	v_mul_f32_e32 v110, v108, v121
	v_fma_f32 v112, -v119, v110, v108
	v_fmac_f32_e32 v110, v112, v121
	v_mul_f32_e32 v112, 0xbfb8aa3b, v102
	v_exp_f32_e32 v112, v112
	v_fma_f32 v108, -v119, v110, v108
	v_div_fmas_f32 v108, v108, v121, v110
	v_div_fixup_f32 v108, v108, v111, v113
	v_add_f32_e32 v110, 1.0, v112
	v_div_scale_f32 v112, s[48:49], v110, v110, v102
	v_rcp_f32_e32 v118, v112
	v_mul_f32_e32 v108, v108, v109
	v_mul_f32_e32 v111, 0xbfb8aa3b, v103
	v_cvt_pk_bf16_f32 v107, v107, v108
	v_fma_f32 v108, -v112, v118, 1.0
	v_exp_f32_e32 v111, v111
	v_fmac_f32_e32 v118, v108, v118
	v_div_scale_f32 v108, vcc, v102, v110, v102
	v_mul_f32_e32 v109, v108, v118
	v_fma_f32 v113, -v112, v109, v108
	v_fmac_f32_e32 v109, v113, v118
	v_add_f32_e32 v111, 1.0, v111
	v_fma_f32 v108, -v112, v109, v108
	v_div_scale_f32 v112, s[48:49], v111, v111, v103
	v_rcp_f32_e32 v113, v112
	v_div_fmas_f32 v108, v108, v118, v109
	v_div_fixup_f32 v102, v108, v110, v102
	v_mul_f32_e32 v98, v102, v98
	v_fma_f32 v102, -v112, v113, 1.0
	v_fmac_f32_e32 v113, v102, v113
	v_div_scale_f32 v102, vcc, v103, v111, v103
	v_mul_f32_e32 v108, v102, v113
	v_fma_f32 v109, -v112, v108, v102
	v_fmac_f32_e32 v108, v109, v113
	v_mul_f32_e32 v109, 0xbfb8aa3b, v104
	v_exp_f32_e32 v109, v109
	v_fma_f32 v102, -v112, v108, v102
	v_div_fmas_f32 v102, v102, v113, v108
	v_div_fixup_f32 v102, v102, v111, v103
	v_add_f32_e32 v109, 1.0, v109
	v_div_scale_f32 v110, s[48:49], v109, v109, v104
	v_rcp_f32_e32 v112, v110
	v_mul_f32_e32 v99, v102, v99
	v_mul_f32_e32 v102, 0xbfb8aa3b, v105
	v_exp_f32_e32 v102, v102
	v_cvt_pk_bf16_f32 v108, v98, v99
	v_fma_f32 v98, -v110, v112, 1.0
	v_fmac_f32_e32 v112, v98, v112
	v_div_scale_f32 v98, vcc, v104, v109, v104
	v_mul_f32_e32 v99, v98, v112
	v_fma_f32 v103, -v110, v99, v98
	v_add_f32_e32 v102, 1.0, v102
	v_fmac_f32_e32 v99, v103, v112
	v_div_scale_f32 v103, s[48:49], v102, v102, v105
	v_fma_f32 v98, -v110, v99, v98
	v_rcp_f32_e32 v110, v103
	v_div_fmas_f32 v98, v98, v112, v99
	v_div_fixup_f32 v98, v98, v109, v104
	v_mul_f32_e32 v98, v98, v100
	v_fma_f32 v99, -v103, v110, 1.0
	v_fmac_f32_e32 v110, v99, v110
	v_div_scale_f32 v99, vcc, v105, v102, v105
	v_mul_f32_e32 v100, v99, v110
	v_fma_f32 v104, -v103, v100, v99
	v_fmac_f32_e32 v100, v104, v110
	v_fma_f32 v99, -v103, v100, v99
	v_div_fmas_f32 v99, v99, v110, v100
	v_mul_f32_e32 v100, 0xbfb8aa3b, v94
	v_exp_f32_e32 v100, v100
	v_div_fixup_f32 v99, v99, v102, v105
	v_mul_f32_e32 v99, v99, v101
	v_cvt_pk_bf16_f32 v109, v98, v99
	v_add_f32_e32 v100, 1.0, v100
	v_div_scale_f32 v101, s[48:49], v100, v100, v94
	v_rcp_f32_e32 v102, v101
	v_or_b32_e32 v98, 16, v148
	v_mad_i64_i32 v[98:99], s[48:49], v98, s64, v[114:115]
	v_lshl_add_u64 v[98:99], v[98:99], 0, v[116:117]
	global_store_dwordx4 v[98:99], v[106:109], off
	v_fma_f32 v98, -v101, v102, 1.0
	v_mul_f32_e32 v103, 0xbfb8aa3b, v95
	v_fmac_f32_e32 v102, v98, v102
	v_div_scale_f32 v98, vcc, v94, v100, v94
	v_exp_f32_e32 v103, v103
	v_mul_f32_e32 v99, v98, v102
	v_fma_f32 v104, -v101, v99, v98
	v_fmac_f32_e32 v99, v104, v102
	v_fma_f32 v98, -v101, v99, v98
	v_add_f32_e32 v101, 1.0, v103
	v_div_scale_f32 v103, s[48:49], v101, v101, v95
	v_rcp_f32_e32 v104, v103
	v_div_fmas_f32 v98, v98, v102, v99
	v_div_fixup_f32 v94, v98, v100, v94
	v_mul_f32_e32 v90, v94, v90
	v_fma_f32 v94, -v103, v104, 1.0
	v_fmac_f32_e32 v104, v94, v104
	v_div_scale_f32 v94, vcc, v95, v101, v95
	v_mul_f32_e32 v98, v94, v104
	v_fma_f32 v99, -v103, v98, v94
	v_fmac_f32_e32 v98, v99, v104
	v_mul_f32_e32 v99, 0xbfb8aa3b, v96
	v_exp_f32_e32 v99, v99
	v_fma_f32 v94, -v103, v98, v94
	v_div_fmas_f32 v94, v94, v104, v98
	v_div_fixup_f32 v94, v94, v101, v95
	v_add_f32_e32 v98, 1.0, v99
	v_div_scale_f32 v99, s[48:49], v98, v98, v96
	v_rcp_f32_e32 v100, v99
	v_mul_f32_e32 v91, v94, v91
	v_mul_f32_e32 v95, 0xbfb8aa3b, v97
	v_cvt_pk_bf16_f32 v90, v90, v91
	v_fma_f32 v91, -v99, v100, 1.0
	v_exp_f32_e32 v95, v95
	v_fmac_f32_e32 v100, v91, v100
	v_div_scale_f32 v91, vcc, v96, v98, v96
	v_mul_f32_e32 v94, v91, v100
	v_fma_f32 v101, -v99, v94, v91
	v_fmac_f32_e32 v94, v101, v100
	v_add_f32_e32 v95, 1.0, v95
	v_fma_f32 v91, -v99, v94, v91
	v_div_scale_f32 v99, s[48:49], v95, v95, v97
	v_rcp_f32_e32 v101, v99
	v_div_fmas_f32 v91, v91, v100, v94
	v_div_fixup_f32 v91, v91, v98, v96
	v_mul_f32_e32 v91, v91, v92
	v_fma_f32 v92, -v99, v101, 1.0
	v_fmac_f32_e32 v101, v92, v101
	v_div_scale_f32 v92, vcc, v97, v95, v97
	v_mul_f32_e32 v94, v92, v101
	v_fma_f32 v96, -v99, v94, v92
	v_fmac_f32_e32 v94, v96, v101
	v_mul_f32_e32 v96, 0xbfb8aa3b, v86
	v_exp_f32_e32 v96, v96
	v_fma_f32 v92, -v99, v94, v92
	v_div_fmas_f32 v92, v92, v101, v94
	v_div_fixup_f32 v92, v92, v95, v97
	v_add_f32_e32 v94, 1.0, v96
	v_div_scale_f32 v96, s[48:49], v94, v94, v86
	v_rcp_f32_e32 v98, v96
	v_mul_f32_e32 v92, v92, v93
	v_mul_f32_e32 v95, 0xbfb8aa3b, v87
	v_cvt_pk_bf16_f32 v91, v91, v92
	v_fma_f32 v92, -v96, v98, 1.0
	v_exp_f32_e32 v95, v95
	v_fmac_f32_e32 v98, v92, v98
	v_div_scale_f32 v92, vcc, v86, v94, v86
	v_mul_f32_e32 v93, v92, v98
	v_fma_f32 v97, -v96, v93, v92
	v_fmac_f32_e32 v93, v97, v98
	v_add_f32_e32 v95, 1.0, v95
	v_fma_f32 v92, -v96, v93, v92
	v_div_scale_f32 v96, s[48:49], v95, v95, v87
	v_rcp_f32_e32 v97, v96
	v_div_fmas_f32 v92, v92, v98, v93
	v_div_fixup_f32 v86, v92, v94, v86
	v_mul_f32_e32 v82, v86, v82
	v_fma_f32 v86, -v96, v97, 1.0
	v_fmac_f32_e32 v97, v86, v97
	v_div_scale_f32 v86, vcc, v87, v95, v87
	v_mul_f32_e32 v92, v86, v97
	v_fma_f32 v93, -v96, v92, v86
	v_fmac_f32_e32 v92, v93, v97
	v_mul_f32_e32 v93, 0xbfb8aa3b, v88
	v_exp_f32_e32 v93, v93
	v_fma_f32 v86, -v96, v92, v86
	v_div_fmas_f32 v86, v86, v97, v92
	v_div_fixup_f32 v86, v86, v95, v87
	v_add_f32_e32 v93, 1.0, v93
	v_div_scale_f32 v94, s[48:49], v93, v93, v88
	v_rcp_f32_e32 v96, v94
	v_mul_f32_e32 v83, v86, v83
	v_mul_f32_e32 v86, 0xbfb8aa3b, v89
	v_exp_f32_e32 v86, v86
	v_cvt_pk_bf16_f32 v92, v82, v83
	v_fma_f32 v82, -v94, v96, 1.0
	v_fmac_f32_e32 v96, v82, v96
	v_div_scale_f32 v82, vcc, v88, v93, v88
	v_mul_f32_e32 v83, v82, v96
	v_fma_f32 v87, -v94, v83, v82
	v_add_f32_e32 v86, 1.0, v86
	v_fmac_f32_e32 v83, v87, v96
	v_div_scale_f32 v87, s[48:49], v86, v86, v89
	v_fma_f32 v82, -v94, v83, v82
	v_rcp_f32_e32 v94, v87
	v_div_fmas_f32 v82, v82, v96, v83
	v_div_fixup_f32 v82, v82, v93, v88
	v_mul_f32_e32 v82, v82, v84
	v_fma_f32 v83, -v87, v94, 1.0
	v_fmac_f32_e32 v94, v83, v94
	v_div_scale_f32 v83, vcc, v89, v86, v89
	v_mul_f32_e32 v84, v83, v94
	v_fma_f32 v88, -v87, v84, v83
	v_fmac_f32_e32 v84, v88, v94
	v_fma_f32 v83, -v87, v84, v83
	v_div_fmas_f32 v83, v83, v94, v84
	v_mul_f32_e32 v84, 0xbfb8aa3b, v78
	v_exp_f32_e32 v84, v84
	v_div_fixup_f32 v83, v83, v86, v89
	v_mul_f32_e32 v83, v83, v85
	v_cvt_pk_bf16_f32 v93, v82, v83
	v_add_f32_e32 v84, 1.0, v84
	v_div_scale_f32 v85, s[48:49], v84, v84, v78
	v_rcp_f32_e32 v86, v85
	v_or_b32_e32 v82, 32, v148
	v_mad_i64_i32 v[82:83], s[48:49], v82, s64, v[114:115]
	v_lshl_add_u64 v[82:83], v[82:83], 0, v[116:117]
	global_store_dwordx4 v[82:83], v[90:93], off
	v_fma_f32 v82, -v85, v86, 1.0
	v_mul_f32_e32 v87, 0xbfb8aa3b, v79
	v_fmac_f32_e32 v86, v82, v86
	v_div_scale_f32 v82, vcc, v78, v84, v78
	v_exp_f32_e32 v87, v87
	v_mul_f32_e32 v83, v82, v86
	v_fma_f32 v88, -v85, v83, v82
	v_fmac_f32_e32 v83, v88, v86
	v_fma_f32 v82, -v85, v83, v82
	v_add_f32_e32 v85, 1.0, v87
	v_div_scale_f32 v87, s[48:49], v85, v85, v79
	v_rcp_f32_e32 v88, v87
	v_div_fmas_f32 v82, v82, v86, v83
	v_div_fixup_f32 v78, v82, v84, v78
	v_mul_f32_e32 v74, v78, v74
	v_fma_f32 v78, -v87, v88, 1.0
	v_fmac_f32_e32 v88, v78, v88
	v_div_scale_f32 v78, vcc, v79, v85, v79
	v_mul_f32_e32 v82, v78, v88
	v_fma_f32 v83, -v87, v82, v78
	v_fmac_f32_e32 v82, v83, v88
	v_mul_f32_e32 v83, 0xbfb8aa3b, v80
	v_exp_f32_e32 v83, v83
	v_fma_f32 v78, -v87, v82, v78
	v_div_fmas_f32 v78, v78, v88, v82
	v_div_fixup_f32 v78, v78, v85, v79
	v_add_f32_e32 v82, 1.0, v83
	v_div_scale_f32 v83, s[48:49], v82, v82, v80
	v_rcp_f32_e32 v84, v83
	v_mul_f32_e32 v75, v78, v75
	v_mul_f32_e32 v79, 0xbfb8aa3b, v81
	v_cvt_pk_bf16_f32 v74, v74, v75
	v_fma_f32 v75, -v83, v84, 1.0
	v_exp_f32_e32 v79, v79
	v_fmac_f32_e32 v84, v75, v84
	v_div_scale_f32 v75, vcc, v80, v82, v80
	v_mul_f32_e32 v78, v75, v84
	v_fma_f32 v85, -v83, v78, v75
	v_fmac_f32_e32 v78, v85, v84
	v_add_f32_e32 v79, 1.0, v79
	v_fma_f32 v75, -v83, v78, v75
	v_div_scale_f32 v83, s[48:49], v79, v79, v81
	v_rcp_f32_e32 v85, v83
	v_div_fmas_f32 v75, v75, v84, v78
	v_div_fixup_f32 v75, v75, v82, v80
	v_mul_f32_e32 v75, v75, v76
	v_fma_f32 v76, -v83, v85, 1.0
	v_fmac_f32_e32 v85, v76, v85
	v_div_scale_f32 v76, vcc, v81, v79, v81
	v_mul_f32_e32 v78, v76, v85
	v_fma_f32 v80, -v83, v78, v76
	v_fmac_f32_e32 v78, v80, v85
	v_mul_f32_e32 v80, 0xbfb8aa3b, v70
	v_exp_f32_e32 v80, v80
	v_fma_f32 v76, -v83, v78, v76
	v_div_fmas_f32 v76, v76, v85, v78
	v_div_fixup_f32 v76, v76, v79, v81
	v_add_f32_e32 v78, 1.0, v80
	v_div_scale_f32 v80, s[48:49], v78, v78, v70
	v_rcp_f32_e32 v82, v80
	v_mul_f32_e32 v76, v76, v77
	v_mul_f32_e32 v79, 0xbfb8aa3b, v71
	v_cvt_pk_bf16_f32 v75, v75, v76
	v_fma_f32 v76, -v80, v82, 1.0
	v_exp_f32_e32 v79, v79
	v_fmac_f32_e32 v82, v76, v82
	v_div_scale_f32 v76, vcc, v70, v78, v70
	v_mul_f32_e32 v77, v76, v82
	v_fma_f32 v81, -v80, v77, v76
	v_fmac_f32_e32 v77, v81, v82
	v_add_f32_e32 v79, 1.0, v79
	v_fma_f32 v76, -v80, v77, v76
	v_div_scale_f32 v80, s[48:49], v79, v79, v71
	v_rcp_f32_e32 v81, v80
	v_div_fmas_f32 v76, v76, v82, v77
	v_div_fixup_f32 v70, v76, v78, v70
	v_mul_f32_e32 v66, v70, v66
	v_fma_f32 v70, -v80, v81, 1.0
	v_fmac_f32_e32 v81, v70, v81
	v_div_scale_f32 v70, vcc, v71, v79, v71
	v_mul_f32_e32 v76, v70, v81
	v_fma_f32 v77, -v80, v76, v70
	v_fmac_f32_e32 v76, v77, v81
	v_mul_f32_e32 v77, 0xbfb8aa3b, v72
	v_exp_f32_e32 v77, v77
	v_fma_f32 v70, -v80, v76, v70
	v_div_fmas_f32 v70, v70, v81, v76
	v_div_fixup_f32 v70, v70, v79, v71
	v_add_f32_e32 v77, 1.0, v77
	v_div_scale_f32 v78, s[48:49], v77, v77, v72
	v_rcp_f32_e32 v80, v78
	v_mul_f32_e32 v67, v70, v67
	v_mul_f32_e32 v70, 0xbfb8aa3b, v73
	v_exp_f32_e32 v70, v70
	v_cvt_pk_bf16_f32 v76, v66, v67
	v_fma_f32 v66, -v78, v80, 1.0
	v_fmac_f32_e32 v80, v66, v80
	v_div_scale_f32 v66, vcc, v72, v77, v72
	v_mul_f32_e32 v67, v66, v80
	v_fma_f32 v71, -v78, v67, v66
	v_add_f32_e32 v70, 1.0, v70
	v_fmac_f32_e32 v67, v71, v80
	v_div_scale_f32 v71, s[48:49], v70, v70, v73
	v_fma_f32 v66, -v78, v67, v66
	v_rcp_f32_e32 v78, v71
	v_div_fmas_f32 v66, v66, v80, v67
	v_div_fixup_f32 v66, v66, v77, v72
	v_mul_f32_e32 v66, v66, v68
	v_fma_f32 v67, -v71, v78, 1.0
	v_fmac_f32_e32 v78, v67, v78
	v_div_scale_f32 v67, vcc, v73, v70, v73
	v_mul_f32_e32 v68, v67, v78
	v_fma_f32 v72, -v71, v68, v67
	v_fmac_f32_e32 v68, v72, v78
	v_fma_f32 v67, -v71, v68, v67
	v_div_fmas_f32 v67, v67, v78, v68
	v_div_fixup_f32 v67, v67, v70, v73
	v_mul_f32_e32 v67, v67, v69
	v_cvt_pk_bf16_f32 v77, v66, v67
	v_mul_f32_e32 v66, 0xbfb8aa3b, v62
	v_exp_f32_e32 v68, v66
	v_or_b32_e32 v66, 48, v148
	v_mad_i64_i32 v[66:67], s[48:49], v66, s64, v[114:115]
	v_add_f32_e32 v68, 1.0, v68
	v_div_scale_f32 v69, s[48:49], v68, v68, v62
	v_rcp_f32_e32 v70, v69
	v_lshl_add_u64 v[66:67], v[66:67], 0, v[116:117]
	global_store_dwordx4 v[66:67], v[74:77], off
	v_mul_f32_e32 v72, 0xbfb8aa3b, v63
	v_fma_f32 v67, -v69, v70, 1.0
	v_fmac_f32_e32 v70, v67, v70
	v_div_scale_f32 v67, vcc, v62, v68, v62
	v_exp_f32_e32 v72, v72
	v_mul_f32_e32 v71, v67, v70
	v_fma_f32 v73, -v69, v71, v67
	v_fmac_f32_e32 v71, v73, v70
	v_fma_f32 v67, -v69, v71, v67
	v_add_f32_e32 v69, 1.0, v72
	v_div_scale_f32 v72, s[48:49], v69, v69, v63
	v_rcp_f32_e32 v73, v72
	v_div_fmas_f32 v67, v67, v70, v71
	v_div_fixup_f32 v62, v67, v68, v62
	v_mul_f32_e32 v58, v62, v58
	v_fma_f32 v62, -v72, v73, 1.0
	v_fmac_f32_e32 v73, v62, v73
	v_div_scale_f32 v62, vcc, v63, v69, v63
	v_mul_f32_e32 v67, v62, v73
	v_fma_f32 v68, -v72, v67, v62
	v_fmac_f32_e32 v67, v68, v73
	v_mul_f32_e32 v68, 0xbfb8aa3b, v64
	v_exp_f32_e32 v68, v68
	v_fma_f32 v62, -v72, v67, v62
	v_div_fmas_f32 v62, v62, v73, v67
	v_div_fixup_f32 v62, v62, v69, v63
	v_add_f32_e32 v67, 1.0, v68
	v_div_scale_f32 v68, s[48:49], v67, v67, v64
	v_rcp_f32_e32 v70, v68
	v_mul_f32_e32 v59, v62, v59
	v_mul_f32_e32 v63, 0xbfb8aa3b, v65
	v_cvt_pk_bf16_f32 v58, v58, v59
	v_fma_f32 v59, -v68, v70, 1.0
	v_exp_f32_e32 v63, v63
	v_fmac_f32_e32 v70, v59, v70
	v_div_scale_f32 v59, vcc, v64, v67, v64
	v_mul_f32_e32 v62, v59, v70
	v_fma_f32 v69, -v68, v62, v59
	v_fmac_f32_e32 v62, v69, v70
	v_add_f32_e32 v63, 1.0, v63
	v_fma_f32 v59, -v68, v62, v59
	v_div_scale_f32 v68, s[48:49], v63, v63, v65
	v_rcp_f32_e32 v69, v68
	v_div_fmas_f32 v59, v59, v70, v62
	v_div_fixup_f32 v59, v59, v67, v64
	v_mul_f32_e32 v59, v59, v60
	v_fma_f32 v60, -v68, v69, 1.0
	v_fmac_f32_e32 v69, v60, v69
	v_div_scale_f32 v60, vcc, v65, v63, v65
	v_mul_f32_e32 v62, v60, v69
	v_fma_f32 v64, -v68, v62, v60
	v_fmac_f32_e32 v62, v64, v69
	v_mul_f32_e32 v64, 0xbfb8aa3b, v54
	v_exp_f32_e32 v64, v64
	v_fma_f32 v60, -v68, v62, v60
	v_div_fmas_f32 v60, v60, v69, v62
	v_div_fixup_f32 v60, v60, v63, v65
	v_add_f32_e32 v62, 1.0, v64
	v_div_scale_f32 v64, s[48:49], v62, v62, v54
	v_rcp_f32_e32 v67, v64
	v_mul_f32_e32 v60, v60, v61
	v_mul_f32_e32 v63, 0xbfb8aa3b, v55
	v_cvt_pk_bf16_f32 v59, v59, v60
	v_fma_f32 v60, -v64, v67, 1.0
	v_exp_f32_e32 v63, v63
	v_fmac_f32_e32 v67, v60, v67
	v_div_scale_f32 v60, vcc, v54, v62, v54
	v_mul_f32_e32 v61, v60, v67
	v_fma_f32 v65, -v64, v61, v60
	v_fmac_f32_e32 v61, v65, v67
	v_add_f32_e32 v63, 1.0, v63
	v_fma_f32 v60, -v64, v61, v60
	v_div_scale_f32 v64, s[48:49], v63, v63, v55
	v_rcp_f32_e32 v65, v64
	v_div_fmas_f32 v60, v60, v67, v61
	v_div_fixup_f32 v54, v60, v62, v54
	v_mul_f32_e32 v50, v54, v50
	v_fma_f32 v54, -v64, v65, 1.0
	v_fmac_f32_e32 v65, v54, v65
	v_div_scale_f32 v54, vcc, v55, v63, v55
	v_mul_f32_e32 v60, v54, v65
	v_fma_f32 v61, -v64, v60, v54
	v_fmac_f32_e32 v60, v61, v65
	v_mul_f32_e32 v61, 0xbfb8aa3b, v56
	v_exp_f32_e32 v61, v61
	v_fma_f32 v54, -v64, v60, v54
	v_div_fmas_f32 v54, v54, v65, v60
	v_div_fixup_f32 v54, v54, v63, v55
	v_add_f32_e32 v61, 1.0, v61
	v_div_scale_f32 v62, s[48:49], v61, v61, v56
	v_rcp_f32_e32 v64, v62
	v_mul_f32_e32 v51, v54, v51
	v_mul_f32_e32 v54, 0xbfb8aa3b, v57
	v_exp_f32_e32 v54, v54
	v_cvt_pk_bf16_f32 v60, v50, v51
	v_fma_f32 v50, -v62, v64, 1.0
	v_fmac_f32_e32 v64, v50, v64
	v_div_scale_f32 v50, vcc, v56, v61, v56
	v_mul_f32_e32 v51, v50, v64
	v_fma_f32 v55, -v62, v51, v50
	v_add_f32_e32 v54, 1.0, v54
	v_fmac_f32_e32 v51, v55, v64
	v_div_scale_f32 v55, s[48:49], v54, v54, v57
	v_fma_f32 v50, -v62, v51, v50
	v_rcp_f32_e32 v62, v55
	v_div_fmas_f32 v50, v50, v64, v51
	v_div_fixup_f32 v50, v50, v61, v56
	v_mul_f32_e32 v50, v50, v52
	v_fma_f32 v51, -v55, v62, 1.0
	v_fmac_f32_e32 v62, v51, v62
	v_div_scale_f32 v51, vcc, v57, v54, v57
	v_mul_f32_e32 v52, v51, v62
	v_fma_f32 v56, -v55, v52, v51
	v_fmac_f32_e32 v52, v56, v62
	v_fma_f32 v51, -v55, v52, v51
	v_div_fmas_f32 v51, v51, v62, v52
	v_mul_f32_e32 v52, 0xbfb8aa3b, v46
	v_exp_f32_e32 v52, v52
	v_div_fixup_f32 v51, v51, v54, v57
	v_mul_f32_e32 v51, v51, v53
	v_add_u32_e32 v66, 0x80, v148
	v_add_f32_e32 v52, 1.0, v52
	v_div_scale_f32 v53, s[48:49], v52, v52, v46
	v_rcp_f32_e32 v54, v53
	v_cvt_pk_bf16_f32 v61, v50, v51
	v_mad_i64_i32 v[50:51], s[48:49], v66, s64, v[114:115]
	v_lshl_add_u64 v[50:51], v[50:51], 0, v[116:117]
	global_store_dwordx4 v[50:51], v[58:61], off
	v_fma_f32 v50, -v53, v54, 1.0
	v_mul_f32_e32 v55, 0xbfb8aa3b, v47
	v_fmac_f32_e32 v54, v50, v54
	v_div_scale_f32 v50, vcc, v46, v52, v46
	v_exp_f32_e32 v55, v55
	v_mul_f32_e32 v51, v50, v54
	v_fma_f32 v56, -v53, v51, v50
	v_fmac_f32_e32 v51, v56, v54
	v_fma_f32 v50, -v53, v51, v50
	v_add_f32_e32 v53, 1.0, v55
	v_div_scale_f32 v55, s[48:49], v53, v53, v47
	v_rcp_f32_e32 v56, v55
	v_div_fmas_f32 v50, v50, v54, v51
	v_div_fixup_f32 v46, v50, v52, v46
	v_mul_f32_e32 v42, v46, v42
	v_fma_f32 v46, -v55, v56, 1.0
	v_fmac_f32_e32 v56, v46, v56
	v_div_scale_f32 v46, vcc, v47, v53, v47
	v_mul_f32_e32 v50, v46, v56
	v_fma_f32 v51, -v55, v50, v46
	v_fmac_f32_e32 v50, v51, v56
	v_mul_f32_e32 v51, 0xbfb8aa3b, v48
	v_exp_f32_e32 v51, v51
	v_fma_f32 v46, -v55, v50, v46
	v_div_fmas_f32 v46, v46, v56, v50
	v_div_fixup_f32 v46, v46, v53, v47
	v_add_f32_e32 v50, 1.0, v51
	v_div_scale_f32 v51, s[48:49], v50, v50, v48
	v_rcp_f32_e32 v52, v51
	v_mul_f32_e32 v43, v46, v43
	v_mul_f32_e32 v47, 0xbfb8aa3b, v49
	v_cvt_pk_bf16_f32 v42, v42, v43
	v_fma_f32 v43, -v51, v52, 1.0
	v_exp_f32_e32 v47, v47
	v_fmac_f32_e32 v52, v43, v52
	v_div_scale_f32 v43, vcc, v48, v50, v48
	v_mul_f32_e32 v46, v43, v52
	v_fma_f32 v53, -v51, v46, v43
	v_fmac_f32_e32 v46, v53, v52
	v_add_f32_e32 v47, 1.0, v47
	v_fma_f32 v43, -v51, v46, v43
	v_div_scale_f32 v51, s[48:49], v47, v47, v49
	v_rcp_f32_e32 v53, v51
	v_div_fmas_f32 v43, v43, v52, v46
	v_div_fixup_f32 v43, v43, v50, v48
	v_mul_f32_e32 v43, v43, v44
	v_fma_f32 v44, -v51, v53, 1.0
	v_fmac_f32_e32 v53, v44, v53
	v_div_scale_f32 v44, vcc, v49, v47, v49
	v_mul_f32_e32 v46, v44, v53
	v_fma_f32 v48, -v51, v46, v44
	v_fmac_f32_e32 v46, v48, v53
	v_mul_f32_e32 v48, 0xbfb8aa3b, v38
	v_exp_f32_e32 v48, v48
	v_fma_f32 v44, -v51, v46, v44
	v_div_fmas_f32 v44, v44, v53, v46
	v_div_fixup_f32 v44, v44, v47, v49
	v_add_f32_e32 v46, 1.0, v48
	v_div_scale_f32 v48, s[48:49], v46, v46, v38
	v_rcp_f32_e32 v50, v48
	v_mul_f32_e32 v44, v44, v45
	v_mul_f32_e32 v47, 0xbfb8aa3b, v39
	v_cvt_pk_bf16_f32 v43, v43, v44
	v_fma_f32 v44, -v48, v50, 1.0
	v_exp_f32_e32 v47, v47
	v_fmac_f32_e32 v50, v44, v50
	v_div_scale_f32 v44, vcc, v38, v46, v38
	v_mul_f32_e32 v45, v44, v50
	v_fma_f32 v49, -v48, v45, v44
	v_fmac_f32_e32 v45, v49, v50
	v_add_f32_e32 v47, 1.0, v47
	v_fma_f32 v44, -v48, v45, v44
	v_div_scale_f32 v48, s[48:49], v47, v47, v39
	v_rcp_f32_e32 v49, v48
	v_div_fmas_f32 v44, v44, v50, v45
	v_div_fixup_f32 v38, v44, v46, v38
	v_mul_f32_e32 v34, v38, v34
	v_fma_f32 v38, -v48, v49, 1.0
	v_fmac_f32_e32 v49, v38, v49
	v_div_scale_f32 v38, vcc, v39, v47, v39
	v_mul_f32_e32 v44, v38, v49
	v_fma_f32 v45, -v48, v44, v38
	v_fmac_f32_e32 v44, v45, v49
	v_mul_f32_e32 v45, 0xbfb8aa3b, v40
	v_exp_f32_e32 v45, v45
	v_fma_f32 v38, -v48, v44, v38
	v_div_fmas_f32 v38, v38, v49, v44
	v_div_fixup_f32 v38, v38, v47, v39
	v_add_f32_e32 v45, 1.0, v45
	v_div_scale_f32 v46, s[48:49], v45, v45, v40
	v_rcp_f32_e32 v48, v46
	v_mul_f32_e32 v35, v38, v35
	v_mul_f32_e32 v38, 0xbfb8aa3b, v41
	v_exp_f32_e32 v38, v38
	v_cvt_pk_bf16_f32 v44, v34, v35
	v_fma_f32 v34, -v46, v48, 1.0
	v_fmac_f32_e32 v48, v34, v48
	v_div_scale_f32 v34, vcc, v40, v45, v40
	v_mul_f32_e32 v35, v34, v48
	v_fma_f32 v39, -v46, v35, v34
	v_add_f32_e32 v38, 1.0, v38
	v_fmac_f32_e32 v35, v39, v48
	v_div_scale_f32 v39, s[48:49], v38, v38, v41
	v_fma_f32 v34, -v46, v35, v34
	v_rcp_f32_e32 v46, v39
	v_div_fmas_f32 v34, v34, v48, v35
	v_div_fixup_f32 v34, v34, v45, v40
	v_mul_f32_e32 v34, v34, v36
	v_fma_f32 v35, -v39, v46, 1.0
	v_fmac_f32_e32 v46, v35, v46
	v_div_scale_f32 v35, vcc, v41, v38, v41
	v_mul_f32_e32 v36, v35, v46
	v_fma_f32 v40, -v39, v36, v35
	v_fmac_f32_e32 v36, v40, v46
	v_fma_f32 v35, -v39, v36, v35
	v_div_fmas_f32 v35, v35, v46, v36
	v_mul_f32_e32 v36, 0xbfb8aa3b, v30
	v_exp_f32_e32 v36, v36
	v_div_fixup_f32 v35, v35, v38, v41
	v_mul_f32_e32 v35, v35, v37
	v_cvt_pk_bf16_f32 v45, v34, v35
	v_add_f32_e32 v36, 1.0, v36
	v_div_scale_f32 v37, s[48:49], v36, v36, v30
	v_rcp_f32_e32 v38, v37
	v_add_u32_e32 v34, 0x90, v148
	v_mad_i64_i32 v[34:35], s[48:49], v34, s64, v[114:115]
	v_lshl_add_u64 v[34:35], v[34:35], 0, v[116:117]
	global_store_dwordx4 v[34:35], v[42:45], off
	v_fma_f32 v34, -v37, v38, 1.0
	v_mul_f32_e32 v39, 0xbfb8aa3b, v31
	v_fmac_f32_e32 v38, v34, v38
	v_div_scale_f32 v34, vcc, v30, v36, v30
	v_exp_f32_e32 v39, v39
	v_mul_f32_e32 v35, v34, v38
	v_fma_f32 v40, -v37, v35, v34
	v_fmac_f32_e32 v35, v40, v38
	v_fma_f32 v34, -v37, v35, v34
	v_add_f32_e32 v37, 1.0, v39
	v_div_scale_f32 v39, s[48:49], v37, v37, v31
	v_rcp_f32_e32 v40, v39
	v_div_fmas_f32 v34, v34, v38, v35
	v_div_fixup_f32 v30, v34, v36, v30
	v_mul_f32_e32 v26, v30, v26
	v_fma_f32 v30, -v39, v40, 1.0
	v_fmac_f32_e32 v40, v30, v40
	v_div_scale_f32 v30, vcc, v31, v37, v31
	v_mul_f32_e32 v34, v30, v40
	v_fma_f32 v35, -v39, v34, v30
	v_fmac_f32_e32 v34, v35, v40
	v_mul_f32_e32 v35, 0xbfb8aa3b, v32
	v_exp_f32_e32 v35, v35
	v_fma_f32 v30, -v39, v34, v30
	v_div_fmas_f32 v30, v30, v40, v34
	v_div_fixup_f32 v30, v30, v37, v31
	v_add_f32_e32 v34, 1.0, v35
	v_div_scale_f32 v35, s[48:49], v34, v34, v32
	v_rcp_f32_e32 v36, v35
	v_mul_f32_e32 v27, v30, v27
	v_mul_f32_e32 v31, 0xbfb8aa3b, v33
	v_cvt_pk_bf16_f32 v26, v26, v27
	v_fma_f32 v27, -v35, v36, 1.0
	v_exp_f32_e32 v31, v31
	v_fmac_f32_e32 v36, v27, v36
	v_div_scale_f32 v27, vcc, v32, v34, v32
	v_mul_f32_e32 v30, v27, v36
	v_fma_f32 v37, -v35, v30, v27
	v_fmac_f32_e32 v30, v37, v36
	v_add_f32_e32 v31, 1.0, v31
	v_fma_f32 v27, -v35, v30, v27
	v_div_scale_f32 v35, s[48:49], v31, v31, v33
	v_rcp_f32_e32 v37, v35
	v_div_fmas_f32 v27, v27, v36, v30
	v_div_fixup_f32 v27, v27, v34, v32
	v_mul_f32_e32 v27, v27, v28
	v_fma_f32 v28, -v35, v37, 1.0
	v_fmac_f32_e32 v37, v28, v37
	v_div_scale_f32 v28, vcc, v33, v31, v33
	v_mul_f32_e32 v30, v28, v37
	v_fma_f32 v32, -v35, v30, v28
	v_fmac_f32_e32 v30, v32, v37
	v_mul_f32_e32 v32, 0xbfb8aa3b, v22
	v_exp_f32_e32 v32, v32
	v_fma_f32 v28, -v35, v30, v28
	v_div_fmas_f32 v28, v28, v37, v30
	v_div_fixup_f32 v28, v28, v31, v33
	v_add_f32_e32 v30, 1.0, v32
	v_div_scale_f32 v32, s[48:49], v30, v30, v22
	v_rcp_f32_e32 v34, v32
	v_mul_f32_e32 v28, v28, v29
	v_mul_f32_e32 v31, 0xbfb8aa3b, v23
	v_cvt_pk_bf16_f32 v27, v27, v28
	v_fma_f32 v28, -v32, v34, 1.0
	v_exp_f32_e32 v31, v31
	v_fmac_f32_e32 v34, v28, v34
	v_div_scale_f32 v28, vcc, v22, v30, v22
	v_mul_f32_e32 v29, v28, v34
	v_fma_f32 v33, -v32, v29, v28
	v_fmac_f32_e32 v29, v33, v34
	v_add_f32_e32 v31, 1.0, v31
	v_fma_f32 v28, -v32, v29, v28
	v_div_scale_f32 v32, s[48:49], v31, v31, v23
	v_rcp_f32_e32 v33, v32
	v_div_fmas_f32 v28, v28, v34, v29
	v_div_fixup_f32 v22, v28, v30, v22
	v_mul_f32_e32 v18, v22, v18
	v_fma_f32 v22, -v32, v33, 1.0
	v_fmac_f32_e32 v33, v22, v33
	v_div_scale_f32 v22, vcc, v23, v31, v23
	v_mul_f32_e32 v28, v22, v33
	v_fma_f32 v29, -v32, v28, v22
	v_fmac_f32_e32 v28, v29, v33
	v_mul_f32_e32 v29, 0xbfb8aa3b, v24
	v_exp_f32_e32 v29, v29
	v_fma_f32 v22, -v32, v28, v22
	v_div_fmas_f32 v22, v22, v33, v28
	v_div_fixup_f32 v22, v22, v31, v23
	v_add_f32_e32 v29, 1.0, v29
	v_div_scale_f32 v30, s[48:49], v29, v29, v24
	v_rcp_f32_e32 v32, v30
	v_mul_f32_e32 v19, v22, v19
	v_mul_f32_e32 v22, 0xbfb8aa3b, v25
	v_exp_f32_e32 v22, v22
	v_cvt_pk_bf16_f32 v28, v18, v19
	v_fma_f32 v18, -v30, v32, 1.0
	v_fmac_f32_e32 v32, v18, v32
	v_div_scale_f32 v18, vcc, v24, v29, v24
	v_mul_f32_e32 v19, v18, v32
	v_fma_f32 v23, -v30, v19, v18
	v_add_f32_e32 v22, 1.0, v22
	v_fmac_f32_e32 v19, v23, v32
	v_div_scale_f32 v23, s[48:49], v22, v22, v25
	v_fma_f32 v18, -v30, v19, v18
	v_rcp_f32_e32 v30, v23
	v_div_fmas_f32 v18, v18, v32, v19
	v_div_fixup_f32 v18, v18, v29, v24
	v_mul_f32_e32 v18, v18, v20
	v_fma_f32 v19, -v23, v30, 1.0
	v_fmac_f32_e32 v30, v19, v30
	v_div_scale_f32 v19, vcc, v25, v22, v25
	v_mul_f32_e32 v20, v19, v30
	v_fma_f32 v24, -v23, v20, v19
	v_fmac_f32_e32 v20, v24, v30
	v_fma_f32 v19, -v23, v20, v19
	v_div_fmas_f32 v19, v19, v30, v20
	v_mul_f32_e32 v20, 0xbfb8aa3b, v14
	v_exp_f32_e32 v20, v20
	v_div_fixup_f32 v19, v19, v22, v25
	v_mul_f32_e32 v19, v19, v21
	v_cvt_pk_bf16_f32 v29, v18, v19
	v_add_f32_e32 v20, 1.0, v20
	v_div_scale_f32 v21, s[48:49], v20, v20, v14
	v_rcp_f32_e32 v22, v21
	v_add_u32_e32 v18, 0xa0, v148
	v_mad_i64_i32 v[18:19], s[48:49], v18, s64, v[114:115]
	v_lshl_add_u64 v[18:19], v[18:19], 0, v[116:117]
	global_store_dwordx4 v[18:19], v[26:29], off
	v_fma_f32 v18, -v21, v22, 1.0
	v_mul_f32_e32 v23, 0xbfb8aa3b, v15
	v_fmac_f32_e32 v22, v18, v22
	v_div_scale_f32 v18, vcc, v14, v20, v14
	v_exp_f32_e32 v23, v23
	v_mul_f32_e32 v19, v18, v22
	v_fma_f32 v24, -v21, v19, v18
	v_fmac_f32_e32 v19, v24, v22
	v_fma_f32 v18, -v21, v19, v18
	v_add_f32_e32 v21, 1.0, v23
	v_div_scale_f32 v23, s[48:49], v21, v21, v15
	v_rcp_f32_e32 v24, v23
	v_div_fmas_f32 v18, v18, v22, v19
	v_div_fixup_f32 v14, v18, v20, v14
	v_mul_f32_e32 v10, v14, v10
	v_fma_f32 v14, -v23, v24, 1.0
	v_fmac_f32_e32 v24, v14, v24
	v_div_scale_f32 v14, vcc, v15, v21, v15
	v_mul_f32_e32 v18, v14, v24
	v_fma_f32 v19, -v23, v18, v14
	v_fmac_f32_e32 v18, v19, v24
	v_mul_f32_e32 v19, 0xbfb8aa3b, v16
	v_exp_f32_e32 v19, v19
	v_fma_f32 v14, -v23, v18, v14
	v_div_fmas_f32 v14, v14, v24, v18
	v_div_fixup_f32 v14, v14, v21, v15
	v_add_f32_e32 v18, 1.0, v19
	v_div_scale_f32 v19, s[48:49], v18, v18, v16
	v_rcp_f32_e32 v20, v19
	v_mul_f32_e32 v11, v14, v11
	v_mul_f32_e32 v15, 0xbfb8aa3b, v17
	v_cvt_pk_bf16_f32 v10, v10, v11
	v_fma_f32 v11, -v19, v20, 1.0
	v_exp_f32_e32 v15, v15
	v_fmac_f32_e32 v20, v11, v20
	v_div_scale_f32 v11, vcc, v16, v18, v16
	v_mul_f32_e32 v14, v11, v20
	v_fma_f32 v21, -v19, v14, v11
	v_fmac_f32_e32 v14, v21, v20
	v_add_f32_e32 v15, 1.0, v15
	v_fma_f32 v11, -v19, v14, v11
	v_div_scale_f32 v19, s[48:49], v15, v15, v17
	v_rcp_f32_e32 v21, v19
	v_div_fmas_f32 v11, v11, v20, v14
	v_div_fixup_f32 v11, v11, v18, v16
	v_mul_f32_e32 v11, v11, v12
	v_fma_f32 v12, -v19, v21, 1.0
	v_fmac_f32_e32 v21, v12, v21
	v_div_scale_f32 v12, vcc, v17, v15, v17
	v_mul_f32_e32 v14, v12, v21
	v_fma_f32 v16, -v19, v14, v12
	v_fmac_f32_e32 v14, v16, v21
	v_mul_f32_e32 v16, 0xbfb8aa3b, v6
	v_exp_f32_e32 v16, v16
	v_fma_f32 v12, -v19, v14, v12
	v_div_fmas_f32 v12, v12, v21, v14
	v_div_fixup_f32 v12, v12, v15, v17
	v_add_f32_e32 v14, 1.0, v16
	v_div_scale_f32 v16, s[48:49], v14, v14, v6
	v_rcp_f32_e32 v18, v16
	v_mul_f32_e32 v12, v12, v13
	v_mul_f32_e32 v15, 0xbfb8aa3b, v7
	v_cvt_pk_bf16_f32 v11, v11, v12
	v_fma_f32 v12, -v16, v18, 1.0
	v_exp_f32_e32 v15, v15
	v_fmac_f32_e32 v18, v12, v18
	v_div_scale_f32 v12, vcc, v6, v14, v6
	v_mul_f32_e32 v13, v12, v18
	v_fma_f32 v17, -v16, v13, v12
	v_fmac_f32_e32 v13, v17, v18
	v_add_f32_e32 v15, 1.0, v15
	v_fma_f32 v12, -v16, v13, v12
	v_div_scale_f32 v16, s[48:49], v15, v15, v7
	v_rcp_f32_e32 v17, v16
	v_div_fmas_f32 v12, v12, v18, v13
	v_div_fixup_f32 v6, v12, v14, v6
	v_mul_f32_e32 v2, v6, v2
	v_fma_f32 v6, -v16, v17, 1.0
	v_fmac_f32_e32 v17, v6, v17
	v_div_scale_f32 v6, vcc, v7, v15, v7
	v_mul_f32_e32 v12, v6, v17
	v_fma_f32 v13, -v16, v12, v6
	v_fmac_f32_e32 v12, v13, v17
	v_mul_f32_e32 v13, 0xbfb8aa3b, v8
	v_exp_f32_e32 v13, v13
	v_fma_f32 v6, -v16, v12, v6
	v_div_fmas_f32 v6, v6, v17, v12
	v_div_fixup_f32 v6, v6, v15, v7
	v_add_f32_e32 v13, 1.0, v13
	v_div_scale_f32 v14, s[48:49], v13, v13, v8
	v_rcp_f32_e32 v16, v14
	v_mul_f32_e32 v3, v6, v3
	v_mul_f32_e32 v6, 0xbfb8aa3b, v9
	v_exp_f32_e32 v6, v6
	v_cvt_pk_bf16_f32 v12, v2, v3
	v_fma_f32 v2, -v14, v16, 1.0
	v_fmac_f32_e32 v16, v2, v16
	v_div_scale_f32 v2, vcc, v8, v13, v8
	v_mul_f32_e32 v3, v2, v16
	v_fma_f32 v7, -v14, v3, v2
	v_add_f32_e32 v6, 1.0, v6
	v_fmac_f32_e32 v3, v7, v16
	v_div_scale_f32 v7, s[48:49], v6, v6, v9
	v_fma_f32 v2, -v14, v3, v2
	v_rcp_f32_e32 v14, v7
	v_div_fmas_f32 v2, v2, v16, v3
	v_div_fixup_f32 v2, v2, v13, v8
	v_mul_f32_e32 v2, v2, v4
	v_fma_f32 v3, -v7, v14, 1.0
	v_fmac_f32_e32 v14, v3, v14
	v_div_scale_f32 v3, vcc, v9, v6, v9
	v_mul_f32_e32 v4, v3, v14
	v_fma_f32 v8, -v7, v4, v3
	v_fmac_f32_e32 v4, v8, v14
	v_fma_f32 v3, -v7, v4, v3
	v_div_fmas_f32 v3, v3, v14, v4
	v_div_fixup_f32 v3, v3, v6, v9
	v_mul_f32_e32 v3, v3, v5
	v_cvt_pk_bf16_f32 v13, v2, v3
	v_add_u32_e32 v2, 0xb0, v148
	v_mad_i64_i32 v[2:3], s[48:49], v2, s64, v[114:115]
	v_lshl_add_u64 v[2:3], v[2:3], 0, v[116:117]
	s_mov_b64 s[48:49], -1
	s_and_b64 vcc, exec, s[44:45]
	global_store_dwordx4 v[2:3], v[10:13], off
	s_cbranch_vccz .LBB0_3204
	s_andn2_b64 vcc, exec, s[6:7]
	s_cbranch_vccnz .LBB0_3203
	s_barrier
	s_branch .LBB0_3203

.LBB0_3339:
	s_or_b64 exec, exec, s[10:11]
	v_mov_b32_e32 v1, v0
	v_mov_b64_e32 v[2:3], s[0:1]
	s_barrier
	global_load_dwordx2 v[2:3], v[2:3], off offset:88 sc0 sc1
	s_waitcnt vmcnt(0)
	v_readfirstlane_b32 s6, v1
	s_ashr_i32 s6, s6, 6
	s_cmp_gt_i32 s6, 15
	s_cbranch_scc1 .LBB0_3342
	v_and_b32_e32 v21, 63, v1
	v_mov_b32_e32 v91, 0
	v_lshlrev_b32_e32 v90, 4, v21
	s_waitcnt lgkmcnt(0)
	v_lshl_add_u64 v[2:3], v[2:3], 0, v[90:91]
	s_movk_i32 s7, 0x3000
	v_add_co_u32_e32 v18, vcc, s7, v2
	v_mbcnt_lo_u32_b32 v1, -1, 0
	s_nop 0
	v_addc_co_u32_e32 v19, vcc, 0, v3, vcc
	global_load_dwordx4 v[2:5], v[18:19], off
	global_load_dwordx4 v[6:9], v[18:19], off offset:1024
	global_load_dwordx4 v[10:13], v[18:19], off offset:2048
	global_load_dwordx4 v[14:17], v[18:19], off offset:3072
	v_mbcnt_hi_u32_b32 v18, -1, v1
	v_and_b32_e32 v1, 64, v18
	v_add_u32_e32 v19, 64, v1
	v_xor_b32_e32 v1, 1, v18
	v_cmp_lt_i32_e32 vcc, v1, v19
	v_xor_b32_e32 v20, 2, v18
	s_lshl_b32 s7, s31, 8
	v_cndmask_b32_e32 v1, v18, v1, vcc
	v_cmp_lt_i32_e32 vcc, v20, v19
	s_lshl_b32 s8, s30, 6
	s_add_i32 s8, s7, s8
	v_cndmask_b32_e32 v20, v18, v20, vcc
	v_lshlrev_b32_e32 v148, 2, v20
	v_xor_b32_e32 v20, 4, v18
	v_cmp_lt_i32_e32 vcc, v20, v19
	s_lshl_b32 s9, s6, 2
	s_add_i32 s6, s9, s8
	v_cndmask_b32_e32 v20, v18, v20, vcc
	v_lshlrev_b32_e32 v149, 2, v20
	v_xor_b32_e32 v20, 8, v18
	v_cmp_lt_i32_e32 vcc, v20, v19
	s_or_b32 s24, s8, 32
	s_lshl_b32 s8, s29, 6
	v_cndmask_b32_e32 v20, v18, v20, vcc
	v_lshlrev_b32_e32 v150, 2, v20
	v_xor_b32_e32 v20, 16, v18
	v_cmp_lt_i32_e32 vcc, v20, v19
	s_add_i32 s7, s7, s8
	s_add_i32 s7, s7, s9
	v_cndmask_b32_e32 v20, v18, v20, vcc
	v_lshlrev_b32_e32 v151, 2, v20
	v_xor_b32_e32 v20, 32, v18
	v_cmp_lt_i32_e32 vcc, v20, v19
	s_lshl_b32 s8, s28, 6
	s_sub_i32 s7, s7, s8
	v_cndmask_b32_e32 v18, v18, v20, vcc
	v_lshlrev_b32_e32 v152, 2, v18
	v_lshlrev_b32_e32 v18, 2, v21
	s_sub_i32 s8, s7, 32
	s_ashr_i32 s7, s6, 31
	v_or_b32_e32 v20, 0x100, v18
	v_or_b32_e32 v22, 0x200, v18
	v_or_b32_e32 v24, 0x300, v18
	s_lshl_b64 s[10:11], s[6:7], 11
	s_lshl_b64 s[6:7], s[6:7], 12
	v_lshlrev_b32_e32 v1, 2, v1
	v_lshl_or_b32 v92, v21, 3, s10
	v_mov_b32_e32 v93, s11
	v_or_b32_e32 v94, s6, v90
	v_mov_b32_e32 v95, s7
	v_mov_b32_e32 v153, 0x358637bd
	s_mov_b32 s25, 0xf800000
	v_mov_b32_e32 v154, 0x260
	v_lshlrev_b32_e32 v90, 2, v18
	s_movk_i32 s26, 0x7fff
	s_mov_b32 s27, 0xffff0000
	s_mov_b32 s28, 0xba00000
	v_lshlrev_b32_e32 v96, 2, v20
	v_lshlrev_b32_e32 v98, 2, v22
	v_mov_b32_e32 v99, v91
	v_lshlrev_b32_e32 v100, 2, v24
	v_mov_b32_e32 v101, v91
	s_mov_b32 s29, 0xba01000
	s_mov_b64 s[16:17], 0x10000
	s_mov_b64 s[18:19], 0x20000
	v_mov_b32_e32 v97, v91
.LBB0_3341:
	v_lshl_add_u64 v[18:19], s[12:13], 0, v[94:95]
	v_lshl_add_u64 v[22:23], s[12:13], 0, v[92:93]
	v_add_co_u32_e32 v20, vcc, 0x7800000, v18
	v_add_co_u32_e64 v102, s[6:7], s28, v22
	s_nop 0
	v_addc_co_u32_e32 v21, vcc, 0, v19, vcc
	v_addc_co_u32_e64 v103, s[6:7], 0, v23, s[6:7]
	v_add_co_u32_e64 v104, s[6:7], s29, v22
	v_add_co_u32_e32 v22, vcc, 0x7801000, v18
	s_nop 0
	v_addc_co_u32_e64 v105, s[6:7], 0, v23, s[6:7]
	global_load_dwordx4 v[78:81], v[20:21], off
	global_load_dwordx4 v[74:77], v[20:21], off offset:1024
	global_load_dwordx4 v[70:73], v[20:21], off offset:2048
	global_load_dwordx4 v[66:69], v[20:21], off offset:3072
	v_addc_co_u32_e32 v23, vcc, 0, v19, vcc
	v_add_co_u32_e32 v20, vcc, 0x7802000, v18
	global_load_dwordx4 v[62:65], v[22:23], off
	global_load_dwordx4 v[58:61], v[22:23], off offset:1024
	global_load_dwordx4 v[54:57], v[22:23], off offset:2048
	global_load_dwordx4 v[50:53], v[22:23], off offset:3072
	v_addc_co_u32_e32 v21, vcc, 0, v19, vcc
	v_add_co_u32_e32 v82, vcc, 0x7803000, v18
	global_load_dwordx4 v[46:49], v[20:21], off
	global_load_dwordx4 v[42:45], v[20:21], off offset:1024
	global_load_dwordx4 v[38:41], v[20:21], off offset:2048
	global_load_dwordx4 v[34:37], v[20:21], off offset:3072
	v_addc_co_u32_e32 v83, vcc, 0, v19, vcc
	global_load_dwordx4 v[30:33], v[82:83], off
	global_load_dwordx4 v[26:29], v[82:83], off offset:1024
	global_load_dwordx4 v[22:25], v[82:83], off offset:2048
	global_load_dwordx4 v[18:21], v[82:83], off offset:3072
	s_add_i32 s30, s8, 32
	s_add_i32 s10, s8, 0xffffc022
	s_ashr_i32 s9, s30, 13
	s_cmpk_lt_i32 s30, 0x4000
	s_cselect_b32 s6, s9, s10
	s_addk_i32 s6, 0x82
	s_mul_hi_i32 s7, s6, 0x9000
	s_mul_i32 s6, s6, 0x9000
	s_add_u32 s6, s14, s6
	s_addc_u32 s7, s15, s7
	s_add_u32 s10, s6, 0x1000
	s_addc_u32 s11, s7, 0
	v_lshl_add_u64 v[124:125], s[6:7], 0, v[90:91]
	v_lshl_add_u64 v[86:87], s[10:11], 0, v[90:91]
	global_load_dwordx4 v[82:85], v[124:125], off
	s_add_i32 s6, s8, 0xffffc023
	global_load_dwordx4 v[86:89], v[86:87], off
	s_cmpk_lt_i32 s30, 0x3fff
	s_cselect_b32 s6, s9, s6
	s_addk_i32 s6, 0x82
	s_mul_hi_i32 s7, s6, 0x9000
	s_mul_i32 s6, s6, 0x9000
	s_add_u32 s6, s14, s6
	s_addc_u32 s7, s15, s7
	v_lshl_add_u64 v[134:135], s[10:11], 0, v[96:97]
	v_lshl_add_u64 v[130:131], s[10:11], 0, v[98:99]
	v_lshl_add_u64 v[128:129], s[10:11], 0, v[100:101]
	s_add_u32 s10, s6, 0x1000
	v_lshl_add_u64 v[110:111], s[6:7], 0, v[90:91]
	s_addc_u32 s11, s7, 0
	s_add_i32 s6, s8, 0xffffc024
	s_cmpk_lt_i32 s30, 0x3ffe
	s_cselect_b32 s6, s9, s6
	s_addk_i32 s6, 0x82
	s_mul_hi_i32 s7, s6, 0x9000
	s_mul_i32 s6, s6, 0x9000
	v_lshl_add_u64 v[126:127], s[10:11], 0, v[90:91]
	v_lshl_add_u64 v[120:121], s[10:11], 0, v[96:97]
	v_lshl_add_u64 v[116:117], s[10:11], 0, v[98:99]
	v_lshl_add_u64 v[112:113], s[10:11], 0, v[100:101]
	s_add_u32 s10, s14, s6
	s_addc_u32 s11, s15, s7
	s_add_u32 s6, s10, 0x1000
	s_addc_u32 s7, s11, 0
	s_addk_i32 s8, 0xc025
	s_cmpk_lt_i32 s30, 0x3ffd
	v_lshl_add_u64 v[138:139], s[6:7], 0, v[90:91]
	v_lshl_add_u64 v[136:137], s[6:7], 0, v[96:97]
	v_lshl_add_u64 v[132:133], s[6:7], 0, v[98:99]
	v_lshl_add_u64 v[122:123], s[6:7], 0, v[100:101]
	s_cselect_b32 s6, s9, s8
	s_addk_i32 s6, 0x82
	s_mul_hi_i32 s7, s6, 0x9000
	s_mul_i32 s6, s6, 0x9000
	s_add_u32 s6, s14, s6
	s_addc_u32 s7, s15, s7
	s_add_u32 s22, s6, 0x1000
	v_lshl_add_u64 v[106:107], s[6:7], 0, v[90:91]
	s_addc_u32 s23, s7, 0
	v_lshl_add_u64 v[108:109], s[10:11], 0, v[90:91]
	v_lshl_add_u64 v[118:119], s[22:23], 0, v[90:91]
	v_lshl_add_u64 v[114:115], s[22:23], 0, v[96:97]
	v_lshl_add_u64 v[92:93], v[92:93], 0, s[16:17]
	s_waitcnt vmcnt(0) lgkmcnt(0)
	v_pk_mul_f32 v[140:141], v[80:81], v[80:81]
	v_pk_mul_f32 v[142:143], v[78:79], v[78:79]
	v_pk_mul_f32 v[144:145], v[76:77], v[76:77]
	v_pk_mul_f32 v[146:147], v[74:75], v[74:75]
	v_mul_f32_e32 v156, v71, v71
	v_mul_f32_e32 v158, v73, v73
	v_mul_f32_e32 v169, v68, v68
	v_mul_f32_e32 v171, v69, v69
	v_pk_mov_b32 v[160:161], v[142:143], v[140:141] op_sel:[1,0]
	v_mov_b32_e32 v143, v141
	v_pk_mov_b32 v[140:141], v[146:147], v[144:145] op_sel:[1,0]
	v_mov_b32_e32 v147, v145
	v_pk_fma_f32 v[144:145], v[70:71], v[70:71], v[156:157] op_sel_hi:[1,1,0]
	v_pk_fma_f32 v[156:157], v[72:73], v[72:73], v[158:159] op_sel_hi:[1,1,0]
	v_pk_mul_f32 v[158:159], v[64:65], v[64:65]
	v_pk_mul_f32 v[162:163], v[62:63], v[62:63]
	v_pk_mul_f32 v[164:165], v[60:61], v[60:61]
	v_pk_mul_f32 v[166:167], v[58:59], v[58:59]
	v_mul_f32_e32 v168, v55, v55
	v_mul_f32_e32 v170, v57, v57
	v_pk_add_f32 v[142:143], v[160:161], v[142:143]
	v_pk_add_f32 v[140:141], v[140:141], v[146:147]
	v_mov_b32_e32 v145, v169
	v_mov_b32_e32 v157, v171
	v_pk_mov_b32 v[146:147], v[162:163], v[158:159] op_sel:[1,0]
	v_mov_b32_e32 v163, v159
	v_pk_mov_b32 v[158:159], v[166:167], v[164:165] op_sel:[1,0]
	v_mov_b32_e32 v167, v165
	v_pk_fma_f32 v[160:161], v[54:55], v[54:55], v[168:169] op_sel_hi:[1,1,0]
	v_pk_fma_f32 v[164:165], v[56:57], v[56:57], v[170:171] op_sel_hi:[1,1,0]
	v_pk_mul_f32 v[168:169], v[48:49], v[48:49]
	v_pk_mul_f32 v[170:171], v[46:47], v[46:47]
	v_pk_mul_f32 v[172:173], v[44:45], v[44:45]
	v_pk_mul_f32 v[174:175], v[42:43], v[42:43]
	v_mul_f32_e32 v155, v66, v66
	v_mul_f32_e32 v179, v67, v67
	v_mul_f32_e32 v177, v52, v52
	v_mul_f32_e32 v184, v53, v53
	v_mul_f32_e32 v176, v39, v39
	v_mul_f32_e32 v178, v41, v41
	v_pk_add_f32 v[180:181], v[142:143], v[142:143] op_sel:[0,1] op_sel_hi:[1,0]
	v_pk_add_f32 v[182:183], v[140:141], v[140:141] op_sel:[0,1] op_sel_hi:[1,0]
	v_pk_add_f32 v[156:157], v[144:145], v[156:157]
	v_pk_add_f32 v[140:141], v[146:147], v[162:163]
	v_pk_add_f32 v[142:143], v[158:159], v[166:167]
	v_pk_mov_b32 v[144:145], v[170:171], v[168:169] op_sel:[1,0]
	v_mov_b32_e32 v171, v169
	v_pk_mov_b32 v[146:147], v[174:175], v[172:173] op_sel:[1,0]
	v_mov_b32_e32 v175, v173
	v_mul_f32_e32 v185, v50, v50
	v_mul_f32_e32 v190, v51, v51
	v_mul_f32_e32 v193, v36, v36
	v_mul_f32_e32 v194, v37, v37
	v_mov_b32_e32 v161, v177
	v_mov_b32_e32 v165, v184
	v_pk_fma_f32 v[158:159], v[38:39], v[38:39], v[176:177] op_sel_hi:[1,1,0]
	v_pk_fma_f32 v[162:163], v[40:41], v[40:41], v[178:179] op_sel_hi:[1,1,0]
	v_pk_mul_f32 v[166:167], v[32:33], v[32:33]
	v_pk_mul_f32 v[168:169], v[30:31], v[30:31]
	v_pk_mul_f32 v[172:173], v[28:29], v[28:29]
	v_pk_mul_f32 v[176:177], v[26:27], v[26:27]
	v_mov_b32_e32 v181, v155
	v_mov_b32_e32 v183, v179
	v_pk_add_f32 v[186:187], v[140:141], v[140:141] op_sel:[0,1] op_sel_hi:[1,0]
	v_pk_add_f32 v[188:189], v[142:143], v[142:143] op_sel:[0,1] op_sel_hi:[1,0]
	v_pk_add_f32 v[144:145], v[144:145], v[170:171]
	v_pk_add_f32 v[146:147], v[146:147], v[174:175]
	v_mul_f32_e32 v191, v34, v34
	v_mul_f32_e32 v192, v35, v35
	v_pk_add_f32 v[160:161], v[160:161], v[164:165]
	v_mov_b32_e32 v159, v193
	v_mov_b32_e32 v163, v194
	v_pk_mov_b32 v[164:165], v[168:169], v[166:167] op_sel:[1,0]
	v_mov_b32_e32 v169, v167
	v_pk_mov_b32 v[166:167], v[176:177], v[172:173] op_sel:[1,0]
	v_mov_b32_e32 v177, v173
	v_pk_add_f32 v[170:171], v[180:181], v[182:183]
	v_mov_b32_e32 v187, v185
	v_mov_b32_e32 v189, v190
	v_pk_add_f32 v[172:173], v[144:145], v[144:145] op_sel:[0,1] op_sel_hi:[1,0]
	v_pk_add_f32 v[174:175], v[146:147], v[146:147] op_sel:[0,1] op_sel_hi:[1,0]
	v_pk_add_f32 v[158:159], v[158:159], v[162:163]
	v_pk_add_f32 v[156:157], v[170:171], v[156:157]
	v_pk_add_f32 v[162:163], v[186:187], v[188:189]
	v_mov_b32_e32 v173, v191
	v_mov_b32_e32 v175, v192
	v_add_f32_e32 v155, v156, v157
	v_pk_add_f32 v[156:157], v[162:163], v[160:161]
	v_pk_add_f32 v[160:161], v[172:173], v[174:175]
	v_add_f32_e32 v162, v156, v157
	v_pk_add_f32 v[156:157], v[160:161], v[158:159]
	ds_bpermute_b32 v158, v1, v155
	ds_bpermute_b32 v159, v1, v162
	v_add_f32_e32 v156, v156, v157
	ds_bpermute_b32 v157, v1, v156
	v_pk_add_f32 v[144:145], v[164:165], v[168:169]
	s_waitcnt lgkmcnt(2)
	v_add_f32_e32 v155, v155, v158
	ds_bpermute_b32 v158, v148, v155
	s_waitcnt lgkmcnt(2)
	v_add_f32_e32 v159, v162, v159
	ds_bpermute_b32 v160, v148, v159
	s_waitcnt lgkmcnt(2)
	v_add_f32_e32 v156, v156, v157
	ds_bpermute_b32 v157, v148, v156
	s_waitcnt lgkmcnt(2)
	v_add_f32_e32 v155, v155, v158
	ds_bpermute_b32 v158, v149, v155
	s_waitcnt lgkmcnt(2)
	v_add_f32_e32 v159, v159, v160
	ds_bpermute_b32 v160, v149, v159
	s_waitcnt lgkmcnt(2)
	v_add_f32_e32 v156, v156, v157
	ds_bpermute_b32 v157, v149, v156
	s_waitcnt lgkmcnt(2)
	v_add_f32_e32 v155, v155, v158
	ds_bpermute_b32 v158, v150, v155
	s_waitcnt lgkmcnt(2)
	v_add_f32_e32 v159, v159, v160
	ds_bpermute_b32 v160, v150, v159
	s_waitcnt lgkmcnt(2)
	v_add_f32_e32 v156, v156, v157
	ds_bpermute_b32 v157, v150, v156
	s_waitcnt lgkmcnt(2)
	v_add_f32_e32 v155, v155, v158
	ds_bpermute_b32 v158, v151, v155
	s_waitcnt lgkmcnt(2)
	v_add_f32_e32 v159, v159, v160
	ds_bpermute_b32 v160, v151, v159
	s_waitcnt lgkmcnt(2)
	v_add_f32_e32 v156, v156, v157
	ds_bpermute_b32 v157, v151, v156
	s_waitcnt lgkmcnt(2)
	v_add_f32_e32 v155, v155, v158
	ds_bpermute_b32 v158, v152, v155
	s_waitcnt lgkmcnt(2)
	v_add_f32_e32 v159, v159, v160
	ds_bpermute_b32 v160, v152, v159
	s_waitcnt lgkmcnt(2)
	v_add_f32_e32 v156, v156, v157
	ds_bpermute_b32 v157, v152, v156
	s_waitcnt lgkmcnt(2)
	v_add_f32_e32 v155, v155, v158
	v_fmamk_f32 v155, v155, 0x3a800000, v153
	s_waitcnt lgkmcnt(1)
	v_add_f32_e32 v158, v159, v160
	v_mul_f32_e32 v159, 0x4f800000, v155
	v_cmp_gt_f32_e32 vcc, s25, v155
	v_fmamk_f32 v158, v158, 0x3a800000, v153
	s_waitcnt lgkmcnt(0)
	v_add_f32_e32 v156, v156, v157
	v_cndmask_b32_e32 v155, v155, v159, vcc
	v_mul_f32_e32 v157, 0x4f800000, v158
	v_cmp_gt_f32_e64 s[6:7], s25, v158
	v_sqrt_f32_e32 v159, v155
	v_fmamk_f32 v156, v156, 0x3a800000, v153
	v_cndmask_b32_e64 v157, v158, v157, s[6:7]
	v_mul_f32_e32 v158, 0x4f800000, v156
	v_cmp_gt_f32_e64 s[8:9], s25, v156
	v_sqrt_f32_e32 v160, v157
	v_add_u32_e32 v161, -1, v159
	v_cndmask_b32_e64 v156, v156, v158, s[8:9]
	v_sqrt_f32_e32 v158, v156
	v_add_u32_e32 v162, 1, v159
	v_fma_f32 v163, -v161, v159, v155
	v_fma_f32 v164, -v162, v159, v155
	v_add_u32_e32 v165, -1, v160
	v_cmp_ge_f32_e64 s[10:11], 0, v163
	v_pk_add_f32 v[146:147], v[166:167], v[176:177]
	v_add_u32_e32 v166, 1, v160
	v_cndmask_b32_e64 v159, v159, v161, s[10:11]
	v_fma_f32 v161, -v165, v160, v157
	v_cmp_lt_f32_e64 s[10:11], 0, v164
	v_fma_f32 v163, -v166, v160, v157
	v_add_u32_e32 v167, -1, v158
	v_cndmask_b32_e64 v159, v159, v162, s[10:11]
	v_cmp_ge_f32_e64 s[10:11], 0, v161
	v_add_u32_e32 v168, 1, v158
	v_fma_f32 v161, -v167, v158, v156
	v_cndmask_b32_e64 v160, v160, v165, s[10:11]
	v_cmp_lt_f32_e64 s[10:11], 0, v163
	v_fma_f32 v162, -v168, v158, v156
	v_mul_f32_e32 v163, 0x37800000, v159
	v_cndmask_b32_e64 v160, v160, v166, s[10:11]
	v_cmp_ge_f32_e64 s[10:11], 0, v161
	v_cndmask_b32_e32 v159, v159, v163, vcc
	v_cmp_class_f32_e32 vcc, v155, v154
	v_cndmask_b32_e64 v158, v158, v167, s[10:11]
	v_cmp_lt_f32_e64 s[10:11], 0, v162
	v_mul_f32_e32 v161, 0x37800000, v160
	v_cndmask_b32_e32 v155, v159, v155, vcc
	v_cndmask_b32_e64 v158, v158, v168, s[10:11]
	v_cndmask_b32_e64 v159, v160, v161, s[6:7]
	v_cmp_class_f32_e32 vcc, v157, v154
	v_mul_f32_e32 v160, 0x37800000, v158
	v_div_scale_f32 v161, s[6:7], v155, v155, 1.0
	v_cndmask_b32_e32 v157, v159, v157, vcc
	v_cndmask_b32_e64 v158, v158, v160, s[8:9]
	v_cmp_class_f32_e32 vcc, v156, v154
	v_rcp_f32_e32 v159, v161
	v_div_scale_f32 v160, s[8:9], v157, v157, 1.0
	v_cndmask_b32_e32 v158, v158, v156, vcc
	v_rcp_f32_e32 v164, v160
	v_div_scale_f32 v165, s[10:11], v158, v158, 1.0
	v_rcp_f32_e32 v167, v165
	v_fma_f32 v156, -v161, v159, 1.0
	v_div_scale_f32 v162, s[6:7], 1.0, v155, 1.0
	v_fmac_f32_e32 v159, v156, v159
	v_fma_f32 v156, -v160, v164, 1.0
	v_mul_f32_e32 v168, v162, v159
	v_div_scale_f32 v163, s[8:9], 1.0, v157, 1.0
	v_fmac_f32_e32 v164, v156, v164
	v_fma_f32 v156, -v165, v167, 1.0
	v_fma_f32 v169, -v161, v168, v162
	v_div_scale_f32 v166, s[10:11], 1.0, v158, 1.0
	v_mul_f32_e32 v170, v163, v164
	v_fmac_f32_e32 v167, v156, v167
	v_fmac_f32_e32 v168, v169, v159
	v_fma_f32 v156, -v160, v170, v163
	v_mul_f32_e32 v169, v166, v167
	v_fma_f32 v161, -v161, v168, v162
	s_mov_b64 vcc, s[6:7]
	v_fmac_f32_e32 v170, v156, v164
	v_fma_f32 v156, -v165, v169, v166
	v_div_fmas_f32 v159, v161, v159, v168
	v_fma_f32 v160, -v160, v170, v163
	v_fmac_f32_e32 v169, v156, v167
	v_div_fixup_f32 v156, v159, v155, 1.0
	s_mov_b64 vcc, s[8:9]
	v_div_fmas_f32 v155, v160, v164, v170
	v_fma_f32 v159, -v165, v169, v166
	v_pk_mul_f32 v[80:81], v[80:81], v[156:157] op_sel_hi:[1,0]
	v_pk_mul_f32 v[78:79], v[78:79], v[156:157] op_sel_hi:[1,0]
	s_mov_b64 vcc, s[10:11]
	v_pk_add_f32 v[88:89], v[88:89], 1.0 op_sel_hi:[1,0]
	v_pk_add_f32 v[86:87], v[86:87], 1.0 op_sel_hi:[1,0]
	v_pk_mul_f32 v[76:77], v[76:77], v[156:157] op_sel_hi:[1,0]
	v_pk_mul_f32 v[74:75], v[74:75], v[156:157] op_sel_hi:[1,0]
	v_pk_mul_f32 v[72:73], v[72:73], v[156:157] op_sel_hi:[1,0]
	v_pk_mul_f32 v[70:71], v[70:71], v[156:157] op_sel_hi:[1,0]
	v_pk_mul_f32 v[68:69], v[68:69], v[156:157] op_sel_hi:[1,0]
	v_pk_mul_f32 v[66:67], v[66:67], v[156:157] op_sel_hi:[1,0]
	v_div_fixup_f32 v156, v155, v157, 1.0
	v_div_fmas_f32 v155, v159, v167, v169
	v_pk_mul_f32 v[78:79], v[78:79], v[2:3]
	v_pk_mul_f32 v[80:81], v[80:81], v[4:5]
	v_pk_mul_f32 v[64:65], v[64:65], v[156:157] op_sel_hi:[1,0]
	v_pk_mul_f32 v[62:63], v[62:63], v[156:157] op_sel_hi:[1,0]
	v_pk_mul_f32 v[60:61], v[60:61], v[156:157] op_sel_hi:[1,0]
	v_pk_mul_f32 v[58:59], v[58:59], v[156:157] op_sel_hi:[1,0]
	v_pk_mul_f32 v[56:57], v[56:57], v[156:157] op_sel_hi:[1,0]
	v_pk_mul_f32 v[54:55], v[54:55], v[156:157] op_sel_hi:[1,0]
	v_pk_mul_f32 v[52:53], v[52:53], v[156:157] op_sel_hi:[1,0]
	v_pk_mul_f32 v[156:157], v[50:51], v[156:157] op_sel_hi:[1,0]
	v_div_fixup_f32 v50, v155, v158, 1.0
	v_pk_fma_f32 v[80:81], v[80:81], v[88:89], v[84:85]
	v_pk_fma_f32 v[78:79], v[78:79], v[86:87], v[82:83]
	v_pk_mul_f32 v[86:87], v[52:53], v[16:17]
	v_pk_mul_f32 v[48:49], v[48:49], v[50:51] op_sel_hi:[1,0]
	v_pk_mul_f32 v[46:47], v[46:47], v[50:51] op_sel_hi:[1,0]
	v_bfe_u32 v51, v78, 16, 1
	v_bfe_u32 v53, v80, 16, 1
	v_pk_mul_f32 v[82:83], v[54:55], v[10:11]
	v_pk_mul_f32 v[84:85], v[156:157], v[14:15]
	v_bfe_u32 v52, v79, 16, 1
	v_bfe_u32 v54, v81, 16, 1
	v_pk_mul_f32 v[88:89], v[46:47], v[2:3]
	v_pk_mul_f32 v[156:157], v[48:49], v[4:5]
	v_add3_u32 v46, v78, v51, s26
	v_add3_u32 v48, v80, v53, s26
	v_add3_u32 v47, v79, v52, s26
	v_add3_u32 v49, v81, v54, s26
	v_lshrrev_b32_e32 v46, 16, v46
	v_lshrrev_b32_e32 v48, 16, v48
	v_and_or_b32 v46, v47, s27, v46
	v_and_or_b32 v47, v49, s27, v48
	global_store_dwordx2 v[102:103], v[46:47], off
	global_load_dwordx4 v[46:49], v[134:135], off
	s_nop 0
	global_load_dwordx4 v[52:55], v[124:125], off offset:1024
	v_pk_mul_f32 v[74:75], v[74:75], v[6:7]
	v_pk_mul_f32 v[76:77], v[76:77], v[8:9]
	v_pk_mul_f32 v[70:71], v[70:71], v[10:11]
	v_pk_mul_f32 v[72:73], v[72:73], v[12:13]
	v_pk_mul_f32 v[66:67], v[66:67], v[14:15]
	v_pk_mul_f32 v[68:69], v[68:69], v[16:17]
	v_pk_mul_f32 v[62:63], v[62:63], v[2:3]
	v_pk_mul_f32 v[64:65], v[64:65], v[4:5]
	v_pk_mul_f32 v[58:59], v[58:59], v[6:7]
	v_pk_mul_f32 v[60:61], v[60:61], v[8:9]
	v_pk_mul_f32 v[56:57], v[56:57], v[12:13]
	v_mul_f32_e32 v178, v23, v23
	v_mul_f32_e32 v184, v25, v25
	v_mul_f32_e32 v195, v18, v18
	v_mul_f32_e32 v196, v19, v19
	v_mul_f32_e32 v197, v20, v20
	v_mul_f32_e32 v198, v21, v21
	v_pk_fma_f32 v[140:141], v[22:23], v[22:23], v[178:179] op_sel_hi:[1,1,0]
	v_pk_fma_f32 v[142:143], v[24:25], v[24:25], v[184:185] op_sel_hi:[1,1,0]
	v_mov_b32_e32 v141, v197
	v_mov_b32_e32 v143, v198
	v_lshl_add_u64 v[94:95], v[94:95], 0, s[18:19]
	s_mov_b32 s8, s30
	s_cmp_lt_i32 s30, s24
	s_waitcnt vmcnt(0) lgkmcnt(0)
	v_pk_add_f32 v[48:49], v[48:49], 1.0 op_sel_hi:[1,0]
	v_pk_add_f32 v[46:47], v[46:47], 1.0 op_sel_hi:[1,0]
	v_pk_fma_f32 v[48:49], v[76:77], v[48:49], v[54:55]
	v_pk_fma_f32 v[46:47], v[74:75], v[46:47], v[52:53]
	v_bfe_u32 v53, v48, 16, 1
	v_bfe_u32 v51, v46, 16, 1
	v_bfe_u32 v52, v47, 16, 1
	v_bfe_u32 v54, v49, 16, 1
	v_add3_u32 v46, v46, v51, s26
	v_add3_u32 v48, v48, v53, s26
	v_add3_u32 v47, v47, v52, s26
	v_add3_u32 v49, v49, v54, s26
	v_lshrrev_b32_e32 v46, 16, v46
	v_lshrrev_b32_e32 v48, 16, v48
	v_and_or_b32 v46, v47, s27, v46
	v_and_or_b32 v47, v49, s27, v48
	global_store_dwordx2 v[102:103], v[46:47], off offset:512
	global_load_dwordx4 v[46:49], v[130:131], off
	s_nop 0
	global_load_dwordx4 v[52:55], v[124:125], off offset:2048
	s_waitcnt vmcnt(0) lgkmcnt(0)
	v_pk_add_f32 v[48:49], v[48:49], 1.0 op_sel_hi:[1,0]
	v_pk_add_f32 v[46:47], v[46:47], 1.0 op_sel_hi:[1,0]
	v_pk_fma_f32 v[48:49], v[72:73], v[48:49], v[54:55]
	v_pk_fma_f32 v[46:47], v[70:71], v[46:47], v[52:53]
	v_bfe_u32 v53, v48, 16, 1
	v_bfe_u32 v51, v46, 16, 1
	v_bfe_u32 v52, v47, 16, 1
	v_bfe_u32 v54, v49, 16, 1
	v_add3_u32 v46, v46, v51, s26
	v_add3_u32 v48, v48, v53, s26
	v_add3_u32 v47, v47, v52, s26
	v_add3_u32 v49, v49, v54, s26
	v_lshrrev_b32_e32 v46, 16, v46
	v_lshrrev_b32_e32 v48, 16, v48
	v_and_or_b32 v46, v47, s27, v46
	v_and_or_b32 v47, v49, s27, v48
	global_store_dwordx2 v[102:103], v[46:47], off offset:1024
	global_load_dwordx4 v[46:49], v[128:129], off
	s_nop 0
	global_load_dwordx4 v[52:55], v[124:125], off offset:3072
	s_waitcnt vmcnt(0) lgkmcnt(0)
	v_pk_add_f32 v[48:49], v[48:49], 1.0 op_sel_hi:[1,0]
	v_pk_add_f32 v[46:47], v[46:47], 1.0 op_sel_hi:[1,0]
	v_pk_fma_f32 v[48:49], v[68:69], v[48:49], v[54:55]
	v_pk_fma_f32 v[46:47], v[66:67], v[46:47], v[52:53]
	v_bfe_u32 v53, v48, 16, 1
	v_bfe_u32 v51, v46, 16, 1
	v_bfe_u32 v52, v47, 16, 1
	v_bfe_u32 v54, v49, 16, 1
	v_add3_u32 v46, v46, v51, s26
	v_add3_u32 v48, v48, v53, s26
	v_add3_u32 v47, v47, v52, s26
	v_add3_u32 v49, v49, v54, s26
	v_lshrrev_b32_e32 v46, 16, v46
	v_lshrrev_b32_e32 v48, 16, v48
	v_and_or_b32 v46, v47, s27, v46
	v_and_or_b32 v47, v49, s27, v48
	global_store_dwordx2 v[102:103], v[46:47], off offset:1536
	global_load_dwordx4 v[46:49], v[126:127], off
	s_nop 0
	global_load_dwordx4 v[52:55], v[110:111], off
	s_waitcnt vmcnt(0) lgkmcnt(0)
	v_pk_add_f32 v[48:49], v[48:49], 1.0 op_sel_hi:[1,0]
	v_pk_add_f32 v[46:47], v[46:47], 1.0 op_sel_hi:[1,0]
	v_pk_fma_f32 v[48:49], v[64:65], v[48:49], v[54:55]
	v_pk_fma_f32 v[46:47], v[62:63], v[46:47], v[52:53]
	v_bfe_u32 v53, v48, 16, 1
	v_bfe_u32 v51, v46, 16, 1
	v_bfe_u32 v52, v47, 16, 1
	v_bfe_u32 v54, v49, 16, 1
	v_add3_u32 v46, v46, v51, s26
	v_add3_u32 v48, v48, v53, s26
	v_add3_u32 v47, v47, v52, s26
	v_add3_u32 v49, v49, v54, s26
	v_lshrrev_b32_e32 v46, 16, v46
	v_lshrrev_b32_e32 v48, 16, v48
	v_and_or_b32 v46, v47, s27, v46
	v_and_or_b32 v47, v49, s27, v48
	global_store_dwordx2 v[102:103], v[46:47], off offset:2048
	global_load_dwordx4 v[46:49], v[120:121], off
	s_nop 0
	global_load_dwordx4 v[52:55], v[110:111], off offset:1024
	s_waitcnt vmcnt(0) lgkmcnt(0)
	v_pk_add_f32 v[48:49], v[48:49], 1.0 op_sel_hi:[1,0]
	v_pk_add_f32 v[46:47], v[46:47], 1.0 op_sel_hi:[1,0]
	v_pk_fma_f32 v[48:49], v[60:61], v[48:49], v[54:55]
	v_pk_fma_f32 v[46:47], v[58:59], v[46:47], v[52:53]
	v_bfe_u32 v53, v48, 16, 1
	v_bfe_u32 v51, v46, 16, 1
	v_bfe_u32 v52, v47, 16, 1
	v_bfe_u32 v54, v49, 16, 1
	v_add3_u32 v46, v46, v51, s26
	v_add3_u32 v48, v48, v53, s26
	v_add3_u32 v47, v47, v52, s26
	v_add3_u32 v49, v49, v54, s26
	v_lshrrev_b32_e32 v46, 16, v46
	v_lshrrev_b32_e32 v48, 16, v48
	v_and_or_b32 v46, v47, s27, v46
	v_and_or_b32 v47, v49, s27, v48
	global_store_dwordx2 v[102:103], v[46:47], off offset:2560
	global_load_dwordx4 v[46:49], v[116:117], off
	s_nop 0
	global_load_dwordx4 v[52:55], v[110:111], off offset:2048
	v_pk_add_f32 v[58:59], v[146:147], v[146:147] op_sel:[0,1] op_sel_hi:[1,0]
	v_pk_add_f32 v[60:61], v[140:141], v[142:143]
	v_mov_b32_e32 v59, v196
	s_waitcnt vmcnt(0) lgkmcnt(0)
	v_pk_add_f32 v[48:49], v[48:49], 1.0 op_sel_hi:[1,0]
	v_pk_add_f32 v[46:47], v[46:47], 1.0 op_sel_hi:[1,0]
	v_pk_fma_f32 v[48:49], v[56:57], v[48:49], v[54:55]
	v_pk_fma_f32 v[46:47], v[82:83], v[46:47], v[52:53]
	v_bfe_u32 v53, v48, 16, 1
	v_bfe_u32 v51, v46, 16, 1
	v_bfe_u32 v52, v47, 16, 1
	v_bfe_u32 v54, v49, 16, 1
	v_add3_u32 v46, v46, v51, s26
	v_add3_u32 v48, v48, v53, s26
	v_add3_u32 v47, v47, v52, s26
	v_add3_u32 v49, v49, v54, s26
	v_lshrrev_b32_e32 v46, 16, v46
	v_lshrrev_b32_e32 v48, 16, v48
	v_and_or_b32 v46, v47, s27, v46
	v_and_or_b32 v47, v49, s27, v48
	global_store_dwordx2 v[102:103], v[46:47], off offset:3072
	global_load_dwordx4 v[46:49], v[112:113], off
	s_nop 0
	global_load_dwordx4 v[52:55], v[110:111], off offset:3072
	v_pk_add_f32 v[56:57], v[144:145], v[144:145] op_sel:[0,1] op_sel_hi:[1,0]
	s_waitcnt vmcnt(0) lgkmcnt(0)
	v_pk_add_f32 v[48:49], v[48:49], 1.0 op_sel_hi:[1,0]
	v_pk_add_f32 v[46:47], v[46:47], 1.0 op_sel_hi:[1,0]
	v_pk_fma_f32 v[48:49], v[86:87], v[48:49], v[54:55]
	v_pk_fma_f32 v[46:47], v[84:85], v[46:47], v[52:53]
	v_bfe_u32 v53, v48, 16, 1
	v_bfe_u32 v51, v46, 16, 1
	v_bfe_u32 v52, v47, 16, 1
	v_bfe_u32 v54, v49, 16, 1
	v_add3_u32 v46, v46, v51, s26
	v_add3_u32 v48, v48, v53, s26
	v_add3_u32 v47, v47, v52, s26
	v_add3_u32 v49, v49, v54, s26
	v_lshrrev_b32_e32 v46, 16, v46
	v_lshrrev_b32_e32 v48, 16, v48
	v_and_or_b32 v46, v47, s27, v46
	v_and_or_b32 v47, v49, s27, v48
	global_store_dwordx2 v[102:103], v[46:47], off offset:3584
	global_load_dwordx4 v[46:49], v[138:139], off
	s_nop 0
	global_load_dwordx4 v[52:55], v[108:109], off
	v_mov_b32_e32 v57, v195
	s_waitcnt vmcnt(0) lgkmcnt(0)
	v_pk_add_f32 v[48:49], v[48:49], 1.0 op_sel_hi:[1,0]
	v_pk_add_f32 v[46:47], v[46:47], 1.0 op_sel_hi:[1,0]
	v_pk_fma_f32 v[48:49], v[156:157], v[48:49], v[54:55]
	v_pk_fma_f32 v[46:47], v[88:89], v[46:47], v[52:53]
	v_bfe_u32 v53, v48, 16, 1
	v_bfe_u32 v51, v46, 16, 1
	v_bfe_u32 v52, v47, 16, 1
	v_bfe_u32 v54, v49, 16, 1
	v_add3_u32 v46, v46, v51, s26
	v_add3_u32 v48, v48, v53, s26
	v_add3_u32 v47, v47, v52, s26
	v_add3_u32 v49, v49, v54, s26
	v_lshrrev_b32_e32 v46, 16, v46
	v_lshrrev_b32_e32 v48, 16, v48
	v_and_or_b32 v46, v47, s27, v46
	v_and_or_b32 v47, v49, s27, v48
	global_store_dwordx2 v[104:105], v[46:47], off
	global_load_dwordx4 v[46:49], v[136:137], off
	s_nop 0
	global_load_dwordx4 v[52:55], v[108:109], off offset:1024
	v_pk_mul_f32 v[44:45], v[44:45], v[50:51] op_sel_hi:[1,0]
	v_pk_mul_f32 v[42:43], v[42:43], v[50:51] op_sel_hi:[1,0]
	v_pk_mul_f32 v[44:45], v[44:45], v[8:9]
	v_pk_mul_f32 v[42:43], v[42:43], v[6:7]
	s_waitcnt vmcnt(0) lgkmcnt(0)
	v_pk_add_f32 v[48:49], v[48:49], 1.0 op_sel_hi:[1,0]
	v_pk_add_f32 v[46:47], v[46:47], 1.0 op_sel_hi:[1,0]
	v_pk_fma_f32 v[44:45], v[44:45], v[48:49], v[54:55]
	v_pk_fma_f32 v[42:43], v[42:43], v[46:47], v[52:53]
	v_bfe_u32 v48, v44, 16, 1
	v_bfe_u32 v46, v42, 16, 1
	v_bfe_u32 v47, v43, 16, 1
	v_bfe_u32 v49, v45, 16, 1
	v_add3_u32 v42, v42, v46, s26
	v_add3_u32 v44, v44, v48, s26
	v_add3_u32 v43, v43, v47, s26
	v_add3_u32 v45, v45, v49, s26
	v_lshrrev_b32_e32 v42, 16, v42
	v_lshrrev_b32_e32 v44, 16, v44
	v_and_or_b32 v42, v43, s27, v42
	v_and_or_b32 v43, v45, s27, v44
	global_store_dwordx2 v[104:105], v[42:43], off offset:512
	global_load_dwordx4 v[42:45], v[132:133], off
	s_nop 0
	global_load_dwordx4 v[46:49], v[108:109], off offset:2048
	v_pk_add_f32 v[52:53], v[56:57], v[58:59]
	s_waitcnt vmcnt(0) lgkmcnt(0)
	v_pk_add_f32 v[44:45], v[44:45], 1.0 op_sel_hi:[1,0]
	v_pk_add_f32 v[52:53], v[52:53], v[60:61]
	v_pk_add_f32 v[42:43], v[42:43], 1.0 op_sel_hi:[1,0]
	v_add_f32_e32 v51, v52, v53
	ds_bpermute_b32 v52, v1, v51
	s_waitcnt lgkmcnt(0)
	v_add_f32_e32 v51, v51, v52
	ds_bpermute_b32 v52, v148, v51
	s_waitcnt lgkmcnt(0)
	v_add_f32_e32 v51, v51, v52
	v_pk_mul_f32 v[40:41], v[40:41], v[50:51] op_sel_hi:[1,0]
	v_pk_mul_f32 v[38:39], v[38:39], v[50:51] op_sel_hi:[1,0]
	v_pk_mul_f32 v[40:41], v[40:41], v[12:13]
	v_pk_mul_f32 v[38:39], v[38:39], v[10:11]
	v_pk_fma_f32 v[40:41], v[40:41], v[44:45], v[48:49]
	v_pk_fma_f32 v[38:39], v[38:39], v[42:43], v[46:47]
	v_bfe_u32 v44, v40, 16, 1
	v_bfe_u32 v42, v38, 16, 1
	v_bfe_u32 v43, v39, 16, 1
	v_bfe_u32 v45, v41, 16, 1
	v_add3_u32 v38, v38, v42, s26
	v_add3_u32 v40, v40, v44, s26
	v_add3_u32 v39, v39, v43, s26
	v_add3_u32 v41, v41, v45, s26
	v_lshrrev_b32_e32 v38, 16, v38
	v_lshrrev_b32_e32 v40, 16, v40
	v_and_or_b32 v38, v39, s27, v38
	v_and_or_b32 v39, v41, s27, v40
	global_store_dwordx2 v[104:105], v[38:39], off offset:1024
	global_load_dwordx4 v[38:41], v[122:123], off
	s_nop 0
	global_load_dwordx4 v[42:45], v[108:109], off offset:3072
	v_pk_mul_f32 v[36:37], v[36:37], v[50:51] op_sel_hi:[1,0]
	v_pk_mul_f32 v[34:35], v[34:35], v[50:51] op_sel_hi:[1,0]
	v_pk_mul_f32 v[36:37], v[36:37], v[16:17]
	v_pk_mul_f32 v[34:35], v[34:35], v[14:15]
	ds_bpermute_b32 v46, v149, v51
	s_waitcnt lgkmcnt(0)
	v_add_f32_e32 v46, v51, v46
	ds_bpermute_b32 v47, v150, v46
	s_waitcnt lgkmcnt(0)
	v_add_f32_e32 v46, v46, v47
	ds_bpermute_b32 v47, v151, v46
	s_waitcnt lgkmcnt(0)
	v_add_f32_e32 v46, v46, v47
	ds_bpermute_b32 v47, v152, v46
	s_waitcnt lgkmcnt(0)
	v_add_f32_e32 v46, v46, v47
	v_fmamk_f32 v46, v46, 0x3a800000, v153
	v_mul_f32_e32 v47, 0x4f800000, v46
	v_cmp_gt_f32_e32 vcc, s25, v46
	s_waitcnt vmcnt(0)
	v_pk_add_f32 v[40:41], v[40:41], 1.0 op_sel_hi:[1,0]
	v_pk_add_f32 v[38:39], v[38:39], 1.0 op_sel_hi:[1,0]
	v_pk_fma_f32 v[36:37], v[36:37], v[40:41], v[44:45]
	v_pk_fma_f32 v[34:35], v[34:35], v[38:39], v[42:43]
	v_bfe_u32 v40, v36, 16, 1
	v_bfe_u32 v38, v34, 16, 1
	v_bfe_u32 v39, v35, 16, 1
	v_bfe_u32 v41, v37, 16, 1
	v_add3_u32 v34, v34, v38, s26
	v_add3_u32 v36, v36, v40, s26
	v_add3_u32 v35, v35, v39, s26
	v_add3_u32 v37, v37, v41, s26
	v_lshrrev_b32_e32 v34, 16, v34
	v_lshrrev_b32_e32 v36, 16, v36
	v_and_or_b32 v34, v35, s27, v34
	v_and_or_b32 v35, v37, s27, v36
	global_store_dwordx2 v[104:105], v[34:35], off offset:1536
	global_load_dwordx4 v[34:37], v[118:119], off
	s_nop 0
	global_load_dwordx4 v[38:41], v[106:107], off
	v_cndmask_b32_e32 v42, v46, v47, vcc
	v_sqrt_f32_e32 v43, v42
	s_waitcnt vmcnt(0) lgkmcnt(0)
	v_pk_add_f32 v[36:37], v[36:37], 1.0 op_sel_hi:[1,0]
	v_add_u32_e32 v44, -1, v43
	v_add_u32_e32 v45, 1, v43
	v_fma_f32 v46, -v44, v43, v42
	v_fma_f32 v47, -v45, v43, v42
	v_cmp_ge_f32_e64 s[6:7], 0, v46
	v_pk_add_f32 v[34:35], v[34:35], 1.0 op_sel_hi:[1,0]
	s_nop 0
	v_cndmask_b32_e64 v43, v43, v44, s[6:7]
	v_cmp_lt_f32_e64 s[6:7], 0, v47
	s_nop 1
	v_cndmask_b32_e64 v43, v43, v45, s[6:7]
	v_mul_f32_e32 v44, 0x37800000, v43
	v_cndmask_b32_e32 v43, v43, v44, vcc
	v_cmp_class_f32_e32 vcc, v42, v154
	s_nop 1
	v_cndmask_b32_e32 v42, v43, v42, vcc
	v_div_scale_f32 v43, s[6:7], v42, v42, 1.0
	v_rcp_f32_e32 v45, v43
	v_div_scale_f32 v44, vcc, 1.0, v42, 1.0
	v_fma_f32 v46, -v43, v45, 1.0
	v_fmac_f32_e32 v45, v46, v45
	v_mul_f32_e32 v46, v44, v45
	v_fma_f32 v47, -v43, v46, v44
	v_fmac_f32_e32 v46, v47, v45
	v_fma_f32 v43, -v43, v46, v44
	v_div_fmas_f32 v43, v43, v45, v46
	v_div_fixup_f32 v42, v43, v42, 1.0
	v_pk_mul_f32 v[32:33], v[32:33], v[42:43] op_sel_hi:[1,0]
	v_pk_mul_f32 v[30:31], v[30:31], v[42:43] op_sel_hi:[1,0]
	v_pk_mul_f32 v[32:33], v[32:33], v[4:5]
	v_pk_mul_f32 v[30:31], v[30:31], v[2:3]
	v_pk_fma_f32 v[32:33], v[32:33], v[36:37], v[40:41]
	v_pk_fma_f32 v[30:31], v[30:31], v[34:35], v[38:39]
	v_bfe_u32 v36, v32, 16, 1
	v_bfe_u32 v34, v30, 16, 1
	v_bfe_u32 v35, v31, 16, 1
	v_bfe_u32 v37, v33, 16, 1
	v_add3_u32 v30, v30, v34, s26
	v_add3_u32 v32, v32, v36, s26
	v_add3_u32 v31, v31, v35, s26
	v_add3_u32 v33, v33, v37, s26
	v_lshrrev_b32_e32 v30, 16, v30
	v_lshrrev_b32_e32 v32, 16, v32
	v_and_or_b32 v30, v31, s27, v30
	v_and_or_b32 v31, v33, s27, v32
	global_store_dwordx2 v[104:105], v[30:31], off offset:2048
	global_load_dwordx4 v[30:33], v[114:115], off
	s_nop 0
	global_load_dwordx4 v[34:37], v[106:107], off offset:1024
	v_pk_mul_f32 v[28:29], v[28:29], v[42:43] op_sel_hi:[1,0]
	v_pk_mul_f32 v[26:27], v[26:27], v[42:43] op_sel_hi:[1,0]
	v_pk_mul_f32 v[28:29], v[28:29], v[8:9]
	v_pk_mul_f32 v[26:27], v[26:27], v[6:7]
	v_lshl_add_u64 v[38:39], s[22:23], 0, v[98:99]
	v_pk_mul_f32 v[24:25], v[24:25], v[42:43] op_sel_hi:[1,0]
	v_pk_mul_f32 v[22:23], v[22:23], v[42:43] op_sel_hi:[1,0]
	v_pk_mul_f32 v[24:25], v[24:25], v[12:13]
	v_pk_mul_f32 v[22:23], v[22:23], v[10:11]
	v_pk_mul_f32 v[20:21], v[20:21], v[42:43] op_sel_hi:[1,0]
	v_pk_mul_f32 v[18:19], v[18:19], v[42:43] op_sel_hi:[1,0]
	v_pk_mul_f32 v[20:21], v[20:21], v[16:17]
	v_pk_mul_f32 v[18:19], v[18:19], v[14:15]
	s_waitcnt vmcnt(0) lgkmcnt(0)
	v_pk_add_f32 v[32:33], v[32:33], 1.0 op_sel_hi:[1,0]
	v_pk_add_f32 v[30:31], v[30:31], 1.0 op_sel_hi:[1,0]
	v_pk_fma_f32 v[28:29], v[28:29], v[32:33], v[36:37]
	v_pk_fma_f32 v[26:27], v[26:27], v[30:31], v[34:35]
	v_bfe_u32 v32, v28, 16, 1
	v_bfe_u32 v30, v26, 16, 1
	v_bfe_u32 v31, v27, 16, 1
	v_bfe_u32 v33, v29, 16, 1
	v_add3_u32 v26, v26, v30, s26
	v_add3_u32 v28, v28, v32, s26
	v_add3_u32 v27, v27, v31, s26
	v_add3_u32 v29, v29, v33, s26
	v_lshrrev_b32_e32 v26, 16, v26
	v_lshrrev_b32_e32 v28, 16, v28
	v_and_or_b32 v26, v27, s27, v26
	v_and_or_b32 v27, v29, s27, v28
	global_store_dwordx2 v[104:105], v[26:27], off offset:2560
	global_load_dwordx4 v[26:29], v[38:39], off
	s_nop 0
	global_load_dwordx4 v[30:33], v[106:107], off offset:2048
	v_lshl_add_u64 v[34:35], s[22:23], 0, v[100:101]
	s_waitcnt vmcnt(0) lgkmcnt(0)
	v_pk_add_f32 v[28:29], v[28:29], 1.0 op_sel_hi:[1,0]
	v_pk_add_f32 v[26:27], v[26:27], 1.0 op_sel_hi:[1,0]
	v_pk_fma_f32 v[24:25], v[24:25], v[28:29], v[32:33]
	v_pk_fma_f32 v[22:23], v[22:23], v[26:27], v[30:31]
	v_bfe_u32 v28, v24, 16, 1
	v_bfe_u32 v26, v22, 16, 1
	v_bfe_u32 v27, v23, 16, 1
	v_bfe_u32 v29, v25, 16, 1
	v_add3_u32 v22, v22, v26, s26
	v_add3_u32 v24, v24, v28, s26
	v_add3_u32 v23, v23, v27, s26
	v_add3_u32 v25, v25, v29, s26
	v_lshrrev_b32_e32 v22, 16, v22
	v_lshrrev_b32_e32 v24, 16, v24
	v_and_or_b32 v22, v23, s27, v22
	v_and_or_b32 v23, v25, s27, v24
	global_store_dwordx2 v[104:105], v[22:23], off offset:3072
	global_load_dwordx4 v[22:25], v[34:35], off
	s_nop 0
	global_load_dwordx4 v[26:29], v[106:107], off offset:3072
	s_waitcnt vmcnt(0) lgkmcnt(0)
	v_pk_add_f32 v[24:25], v[24:25], 1.0 op_sel_hi:[1,0]
	v_pk_add_f32 v[22:23], v[22:23], 1.0 op_sel_hi:[1,0]
	v_pk_fma_f32 v[20:21], v[20:21], v[24:25], v[28:29]
	v_pk_fma_f32 v[18:19], v[18:19], v[22:23], v[26:27]
	v_bfe_u32 v24, v20, 16, 1
	v_bfe_u32 v22, v18, 16, 1
	v_bfe_u32 v23, v19, 16, 1
	v_bfe_u32 v25, v21, 16, 1
	v_add3_u32 v18, v18, v22, s26
	v_add3_u32 v20, v20, v24, s26
	v_add3_u32 v19, v19, v23, s26
	v_add3_u32 v21, v21, v25, s26
	v_lshrrev_b32_e32 v18, 16, v18
	v_lshrrev_b32_e32 v20, 16, v20
	v_and_or_b32 v18, v19, s27, v18
	v_and_or_b32 v19, v21, s27, v20
	global_store_dwordx2 v[104:105], v[18:19], off offset:3584
	s_cbranch_scc1 .LBB0_3341

.LBB0_3404:
	v_mul_f32_e32 v133, 0xbfb8aa3b, v126
	v_exp_f32_e32 v133, v133
	s_lshl_b32 s5, s40, 7
	s_or_b32 s5, s34, s5
	v_or_b32_e32 v134, s5, v131
	v_add_f32_e32 v133, 1.0, v133
	v_div_scale_f32 v137, s[8:9], v133, v133, v126
	v_rcp_f32_e32 v138, v137
	v_mul_f32_e32 v140, 0xbfb8aa3b, v127
	v_exp_f32_e32 v140, v140
	v_add_u32_e32 v136, 0x4000, v1
	v_fma_f32 v131, -v137, v138, 1.0
	v_fmac_f32_e32 v138, v131, v138
	v_div_scale_f32 v131, vcc, v126, v133, v126
	v_mul_f32_e32 v139, v131, v138
	v_fma_f32 v141, -v137, v139, v131
	v_fmac_f32_e32 v139, v141, v138
	v_fma_f32 v131, -v137, v139, v131
	v_add_f32_e32 v137, 1.0, v140
	v_div_scale_f32 v140, s[8:9], v137, v137, v127
	v_rcp_f32_e32 v141, v140
	v_div_fmas_f32 v131, v131, v138, v139
	v_div_fixup_f32 v126, v131, v133, v126
	v_mul_f32_e32 v122, v126, v122
	v_fma_f32 v126, -v140, v141, 1.0
	v_fmac_f32_e32 v141, v126, v141
	v_div_scale_f32 v126, vcc, v127, v137, v127
	v_mul_f32_e32 v131, v126, v141
	v_fma_f32 v133, -v140, v131, v126
	v_fmac_f32_e32 v131, v133, v141
	v_mul_f32_e32 v133, 0xbfb8aa3b, v128
	v_exp_f32_e32 v133, v133
	v_fma_f32 v126, -v140, v131, v126
	v_div_fmas_f32 v126, v126, v141, v131
	v_div_fixup_f32 v126, v126, v137, v127
	v_add_f32_e32 v131, 1.0, v133
	v_div_scale_f32 v133, s[8:9], v131, v131, v128
	v_rcp_f32_e32 v138, v133
	v_mul_f32_e32 v123, v126, v123
	v_mul_f32_e32 v127, 0xbfb8aa3b, v129
	v_cvt_pk_bf16_f32 v122, v122, v123
	v_fma_f32 v123, -v133, v138, 1.0
	v_exp_f32_e32 v127, v127
	v_fmac_f32_e32 v138, v123, v138
	v_div_scale_f32 v123, vcc, v128, v131, v128
	v_mul_f32_e32 v126, v123, v138
	v_fma_f32 v137, -v133, v126, v123
	v_fmac_f32_e32 v126, v137, v138
	v_add_f32_e32 v127, 1.0, v127
	v_fma_f32 v123, -v133, v126, v123
	v_div_scale_f32 v133, s[8:9], v127, v127, v129
	v_rcp_f32_e32 v137, v133
	v_div_fmas_f32 v123, v123, v138, v126
	v_div_fixup_f32 v123, v123, v131, v128
	v_mul_f32_e32 v123, v123, v124
	v_fma_f32 v124, -v133, v137, 1.0
	v_fmac_f32_e32 v137, v124, v137
	v_div_scale_f32 v124, vcc, v129, v127, v129
	v_mul_f32_e32 v126, v124, v137
	v_fma_f32 v128, -v133, v126, v124
	v_fmac_f32_e32 v126, v128, v137
	v_mul_f32_e32 v128, 0xbfb8aa3b, v118
	v_exp_f32_e32 v128, v128
	v_fma_f32 v124, -v133, v126, v124
	v_div_fmas_f32 v124, v124, v137, v126
	v_div_fixup_f32 v124, v124, v127, v129
	v_add_f32_e32 v126, 1.0, v128
	v_div_scale_f32 v128, s[8:9], v126, v126, v118
	v_rcp_f32_e32 v131, v128
	v_mul_f32_e32 v124, v124, v125
	v_mul_f32_e32 v127, 0xbfb8aa3b, v119
	v_cvt_pk_bf16_f32 v123, v123, v124
	v_fma_f32 v124, -v128, v131, 1.0
	v_exp_f32_e32 v127, v127
	v_fmac_f32_e32 v131, v124, v131
	v_div_scale_f32 v124, vcc, v118, v126, v118
	v_mul_f32_e32 v125, v124, v131
	v_fma_f32 v129, -v128, v125, v124
	v_fmac_f32_e32 v125, v129, v131
	v_add_f32_e32 v127, 1.0, v127
	v_fma_f32 v124, -v128, v125, v124
	v_div_scale_f32 v128, s[8:9], v127, v127, v119
	v_rcp_f32_e32 v129, v128
	v_div_fmas_f32 v124, v124, v131, v125
	v_div_fixup_f32 v118, v124, v126, v118
	v_mul_f32_e32 v114, v118, v114
	v_fma_f32 v118, -v128, v129, 1.0
	v_fmac_f32_e32 v129, v118, v129
	v_div_scale_f32 v118, vcc, v119, v127, v119
	v_mul_f32_e32 v124, v118, v129
	v_fma_f32 v125, -v128, v124, v118
	v_fmac_f32_e32 v124, v125, v129
	v_mul_f32_e32 v125, 0xbfb8aa3b, v120
	v_exp_f32_e32 v125, v125
	v_fma_f32 v118, -v128, v124, v118
	v_div_fmas_f32 v118, v118, v129, v124
	v_div_fixup_f32 v118, v118, v127, v119
	v_add_f32_e32 v125, 1.0, v125
	v_div_scale_f32 v126, s[8:9], v125, v125, v120
	v_rcp_f32_e32 v128, v126
	v_mul_f32_e32 v115, v118, v115
	v_mul_f32_e32 v118, 0xbfb8aa3b, v121
	v_exp_f32_e32 v118, v118
	v_cvt_pk_bf16_f32 v124, v114, v115
	v_fma_f32 v114, -v126, v128, 1.0
	v_fmac_f32_e32 v128, v114, v128
	v_div_scale_f32 v114, vcc, v120, v125, v120
	v_mul_f32_e32 v115, v114, v128
	v_fma_f32 v119, -v126, v115, v114
	v_add_f32_e32 v118, 1.0, v118
	v_fmac_f32_e32 v115, v119, v128
	v_div_scale_f32 v119, s[8:9], v118, v118, v121
	v_fma_f32 v114, -v126, v115, v114
	v_rcp_f32_e32 v126, v119
	v_div_fmas_f32 v114, v114, v128, v115
	v_div_fixup_f32 v114, v114, v125, v120
	v_mul_f32_e32 v114, v114, v116
	v_fma_f32 v115, -v119, v126, 1.0
	v_fmac_f32_e32 v126, v115, v126
	v_div_scale_f32 v115, vcc, v121, v118, v121
	v_mul_f32_e32 v116, v115, v126
	v_fma_f32 v120, -v119, v116, v115
	v_fmac_f32_e32 v116, v120, v126
	v_fma_f32 v115, -v119, v116, v115
	v_div_fmas_f32 v115, v115, v126, v116
	v_div_fixup_f32 v115, v115, v118, v121
	v_mul_f32_e32 v115, v115, v117
	v_cvt_pk_bf16_f32 v125, v114, v115
	v_mul_f32_e32 v114, 0xbfb8aa3b, v110
	v_exp_f32_e32 v116, v114
	v_ashrrev_i32_e32 v135, 31, v134
	s_movk_i32 s5, 0x1600
	v_mov_b64_e32 v[114:115], s[18:19]
	v_add_f32_e32 v120, 1.0, v116
	v_div_scale_f32 v121, s[8:9], v120, v120, v110
	v_rcp_f32_e32 v126, v121
	v_mad_i64_i32 v[118:119], s[8:9], v136, s5, v[114:115]
	v_lshlrev_b64 v[116:117], 1, v[134:135]
	v_lshl_add_u64 v[118:119], v[118:119], 0, v[116:117]
	global_store_dwordx4 v[118:119], v[122:125], off
	v_fma_f32 v118, -v121, v126, 1.0
	v_fmac_f32_e32 v126, v118, v126
	v_mul_f32_e32 v122, 0xbfb8aa3b, v111
	v_div_scale_f32 v118, vcc, v110, v120, v110
	v_exp_f32_e32 v122, v122
	v_mul_f32_e32 v119, v118, v126
	v_fma_f32 v123, -v121, v119, v118
	v_fmac_f32_e32 v119, v123, v126
	v_fma_f32 v118, -v121, v119, v118
	v_add_f32_e32 v121, 1.0, v122
	v_div_scale_f32 v122, s[8:9], v121, v121, v111
	v_rcp_f32_e32 v123, v122
	v_div_fmas_f32 v118, v118, v126, v119
	v_div_fixup_f32 v110, v118, v120, v110
	v_mul_f32_e32 v106, v110, v106
	v_fma_f32 v110, -v122, v123, 1.0
	v_fmac_f32_e32 v123, v110, v123
	v_div_scale_f32 v110, vcc, v111, v121, v111
	v_mul_f32_e32 v118, v110, v123
	v_fma_f32 v119, -v122, v118, v110
	v_fmac_f32_e32 v118, v119, v123
	v_mul_f32_e32 v119, 0xbfb8aa3b, v112
	v_exp_f32_e32 v119, v119
	v_fma_f32 v110, -v122, v118, v110
	v_div_fmas_f32 v110, v110, v123, v118
	v_div_fixup_f32 v110, v110, v121, v111
	v_add_f32_e32 v118, 1.0, v119
	v_div_scale_f32 v119, s[8:9], v118, v118, v112
	v_rcp_f32_e32 v120, v119
	v_mul_f32_e32 v107, v110, v107
	v_mul_f32_e32 v111, 0xbfb8aa3b, v113
	v_cvt_pk_bf16_f32 v106, v106, v107
	v_fma_f32 v107, -v119, v120, 1.0
	v_exp_f32_e32 v111, v111
	v_fmac_f32_e32 v120, v107, v120
	v_div_scale_f32 v107, vcc, v112, v118, v112
	v_mul_f32_e32 v110, v107, v120
	v_fma_f32 v121, -v119, v110, v107
	v_fmac_f32_e32 v110, v121, v120
	v_add_f32_e32 v111, 1.0, v111
	v_fma_f32 v107, -v119, v110, v107
	v_div_scale_f32 v119, s[8:9], v111, v111, v113
	v_rcp_f32_e32 v121, v119
	v_div_fmas_f32 v107, v107, v120, v110
	v_div_fixup_f32 v107, v107, v118, v112
	v_mul_f32_e32 v107, v107, v108
	v_fma_f32 v108, -v119, v121, 1.0
	v_fmac_f32_e32 v121, v108, v121
	v_div_scale_f32 v108, vcc, v113, v111, v113
	v_mul_f32_e32 v110, v108, v121
	v_fma_f32 v112, -v119, v110, v108
	v_fmac_f32_e32 v110, v112, v121
	v_mul_f32_e32 v112, 0xbfb8aa3b, v102
	v_exp_f32_e32 v112, v112
	v_fma_f32 v108, -v119, v110, v108
	v_div_fmas_f32 v108, v108, v121, v110
	v_div_fixup_f32 v108, v108, v111, v113
	v_add_f32_e32 v110, 1.0, v112
	v_div_scale_f32 v112, s[8:9], v110, v110, v102
	v_rcp_f32_e32 v118, v112
	v_mul_f32_e32 v108, v108, v109
	v_mul_f32_e32 v111, 0xbfb8aa3b, v103
	v_cvt_pk_bf16_f32 v107, v107, v108
	v_fma_f32 v108, -v112, v118, 1.0
	v_exp_f32_e32 v111, v111
	v_fmac_f32_e32 v118, v108, v118
	v_div_scale_f32 v108, vcc, v102, v110, v102
	v_mul_f32_e32 v109, v108, v118
	v_fma_f32 v113, -v112, v109, v108
	v_fmac_f32_e32 v109, v113, v118
	v_add_f32_e32 v111, 1.0, v111
	v_fma_f32 v108, -v112, v109, v108
	v_div_scale_f32 v112, s[8:9], v111, v111, v103
	v_rcp_f32_e32 v113, v112
	v_div_fmas_f32 v108, v108, v118, v109
	v_div_fixup_f32 v102, v108, v110, v102
	v_mul_f32_e32 v98, v102, v98
	v_fma_f32 v102, -v112, v113, 1.0
	v_fmac_f32_e32 v113, v102, v113
	v_div_scale_f32 v102, vcc, v103, v111, v103
	v_mul_f32_e32 v108, v102, v113
	v_fma_f32 v109, -v112, v108, v102
	v_fmac_f32_e32 v108, v109, v113
	v_mul_f32_e32 v109, 0xbfb8aa3b, v104
	v_exp_f32_e32 v109, v109
	v_fma_f32 v102, -v112, v108, v102
	v_div_fmas_f32 v102, v102, v113, v108
	v_div_fixup_f32 v102, v102, v111, v103
	v_add_f32_e32 v109, 1.0, v109
	v_div_scale_f32 v110, s[8:9], v109, v109, v104
	v_rcp_f32_e32 v112, v110
	v_mul_f32_e32 v99, v102, v99
	v_mul_f32_e32 v102, 0xbfb8aa3b, v105
	v_exp_f32_e32 v102, v102
	v_cvt_pk_bf16_f32 v108, v98, v99
	v_fma_f32 v98, -v110, v112, 1.0
	v_fmac_f32_e32 v112, v98, v112
	v_div_scale_f32 v98, vcc, v104, v109, v104
	v_mul_f32_e32 v99, v98, v112
	v_fma_f32 v103, -v110, v99, v98
	v_add_f32_e32 v102, 1.0, v102
	v_fmac_f32_e32 v99, v103, v112
	v_div_scale_f32 v103, s[8:9], v102, v102, v105
	v_fma_f32 v98, -v110, v99, v98
	v_rcp_f32_e32 v110, v103
	v_div_fmas_f32 v98, v98, v112, v99
	v_div_fixup_f32 v98, v98, v109, v104
	v_mul_f32_e32 v98, v98, v100
	v_fma_f32 v99, -v103, v110, 1.0
	v_fmac_f32_e32 v110, v99, v110
	v_div_scale_f32 v99, vcc, v105, v102, v105
	v_mul_f32_e32 v100, v99, v110
	v_fma_f32 v104, -v103, v100, v99
	v_fmac_f32_e32 v100, v104, v110
	v_fma_f32 v99, -v103, v100, v99
	v_div_fmas_f32 v99, v99, v110, v100
	v_mul_f32_e32 v100, 0xbfb8aa3b, v94
	v_exp_f32_e32 v100, v100
	v_div_fixup_f32 v99, v99, v102, v105
	v_mul_f32_e32 v99, v99, v101
	v_cvt_pk_bf16_f32 v109, v98, v99
	v_add_f32_e32 v100, 1.0, v100
	v_div_scale_f32 v101, s[8:9], v100, v100, v94
	v_rcp_f32_e32 v102, v101
	v_add_u32_e32 v98, 0x4010, v1
	v_mad_i64_i32 v[98:99], s[8:9], v98, s5, v[114:115]
	v_lshl_add_u64 v[98:99], v[98:99], 0, v[116:117]
	global_store_dwordx4 v[98:99], v[106:109], off
	v_fma_f32 v98, -v101, v102, 1.0
	v_mul_f32_e32 v103, 0xbfb8aa3b, v95
	v_fmac_f32_e32 v102, v98, v102
	v_div_scale_f32 v98, vcc, v94, v100, v94
	v_exp_f32_e32 v103, v103
	v_mul_f32_e32 v99, v98, v102
	v_fma_f32 v104, -v101, v99, v98
	v_fmac_f32_e32 v99, v104, v102
	v_fma_f32 v98, -v101, v99, v98
	v_add_f32_e32 v101, 1.0, v103
	v_div_scale_f32 v103, s[8:9], v101, v101, v95
	v_rcp_f32_e32 v104, v103
	v_div_fmas_f32 v98, v98, v102, v99
	v_div_fixup_f32 v94, v98, v100, v94
	v_mul_f32_e32 v90, v94, v90
	v_fma_f32 v94, -v103, v104, 1.0
	v_fmac_f32_e32 v104, v94, v104
	v_div_scale_f32 v94, vcc, v95, v101, v95
	v_mul_f32_e32 v98, v94, v104
	v_fma_f32 v99, -v103, v98, v94
	v_fmac_f32_e32 v98, v99, v104
	v_mul_f32_e32 v99, 0xbfb8aa3b, v96
	v_exp_f32_e32 v99, v99
	v_fma_f32 v94, -v103, v98, v94
	v_div_fmas_f32 v94, v94, v104, v98
	v_div_fixup_f32 v94, v94, v101, v95
	v_add_f32_e32 v98, 1.0, v99
	v_div_scale_f32 v99, s[8:9], v98, v98, v96
	v_rcp_f32_e32 v100, v99
	v_mul_f32_e32 v91, v94, v91
	v_mul_f32_e32 v95, 0xbfb8aa3b, v97
	v_cvt_pk_bf16_f32 v90, v90, v91
	v_fma_f32 v91, -v99, v100, 1.0
	v_exp_f32_e32 v95, v95
	v_fmac_f32_e32 v100, v91, v100
	v_div_scale_f32 v91, vcc, v96, v98, v96
	v_mul_f32_e32 v94, v91, v100
	v_fma_f32 v101, -v99, v94, v91
	v_fmac_f32_e32 v94, v101, v100
	v_add_f32_e32 v95, 1.0, v95
	v_fma_f32 v91, -v99, v94, v91
	v_div_scale_f32 v99, s[8:9], v95, v95, v97
	v_rcp_f32_e32 v101, v99
	v_div_fmas_f32 v91, v91, v100, v94
	v_div_fixup_f32 v91, v91, v98, v96
	v_mul_f32_e32 v91, v91, v92
	v_fma_f32 v92, -v99, v101, 1.0
	v_fmac_f32_e32 v101, v92, v101
	v_div_scale_f32 v92, vcc, v97, v95, v97
	v_mul_f32_e32 v94, v92, v101
	v_fma_f32 v96, -v99, v94, v92
	v_fmac_f32_e32 v94, v96, v101
	v_mul_f32_e32 v96, 0xbfb8aa3b, v86
	v_exp_f32_e32 v96, v96
	v_fma_f32 v92, -v99, v94, v92
	v_div_fmas_f32 v92, v92, v101, v94
	v_div_fixup_f32 v92, v92, v95, v97
	v_add_f32_e32 v94, 1.0, v96
	v_div_scale_f32 v96, s[8:9], v94, v94, v86
	v_rcp_f32_e32 v98, v96
	v_mul_f32_e32 v92, v92, v93
	v_mul_f32_e32 v95, 0xbfb8aa3b, v87
	v_cvt_pk_bf16_f32 v91, v91, v92
	v_fma_f32 v92, -v96, v98, 1.0
	v_exp_f32_e32 v95, v95
	v_fmac_f32_e32 v98, v92, v98
	v_div_scale_f32 v92, vcc, v86, v94, v86
	v_mul_f32_e32 v93, v92, v98
	v_fma_f32 v97, -v96, v93, v92
	v_fmac_f32_e32 v93, v97, v98
	v_add_f32_e32 v95, 1.0, v95
	v_fma_f32 v92, -v96, v93, v92
	v_div_scale_f32 v96, s[8:9], v95, v95, v87
	v_rcp_f32_e32 v97, v96
	v_div_fmas_f32 v92, v92, v98, v93
	v_div_fixup_f32 v86, v92, v94, v86
	v_mul_f32_e32 v82, v86, v82
	v_fma_f32 v86, -v96, v97, 1.0
	v_fmac_f32_e32 v97, v86, v97
	v_div_scale_f32 v86, vcc, v87, v95, v87
	v_mul_f32_e32 v92, v86, v97
	v_fma_f32 v93, -v96, v92, v86
	v_fmac_f32_e32 v92, v93, v97
	v_mul_f32_e32 v93, 0xbfb8aa3b, v88
	v_exp_f32_e32 v93, v93
	v_fma_f32 v86, -v96, v92, v86
	v_div_fmas_f32 v86, v86, v97, v92
	v_div_fixup_f32 v86, v86, v95, v87
	v_add_f32_e32 v93, 1.0, v93
	v_div_scale_f32 v94, s[8:9], v93, v93, v88
	v_rcp_f32_e32 v96, v94
	v_mul_f32_e32 v83, v86, v83
	v_mul_f32_e32 v86, 0xbfb8aa3b, v89
	v_exp_f32_e32 v86, v86
	v_cvt_pk_bf16_f32 v92, v82, v83
	v_fma_f32 v82, -v94, v96, 1.0
	v_fmac_f32_e32 v96, v82, v96
	v_div_scale_f32 v82, vcc, v88, v93, v88
	v_mul_f32_e32 v83, v82, v96
	v_fma_f32 v87, -v94, v83, v82
	v_add_f32_e32 v86, 1.0, v86
	v_fmac_f32_e32 v83, v87, v96
	v_div_scale_f32 v87, s[8:9], v86, v86, v89
	v_fma_f32 v82, -v94, v83, v82
	v_rcp_f32_e32 v94, v87
	v_div_fmas_f32 v82, v82, v96, v83
	v_div_fixup_f32 v82, v82, v93, v88
	v_mul_f32_e32 v82, v82, v84
	v_fma_f32 v83, -v87, v94, 1.0
	v_fmac_f32_e32 v94, v83, v94
	v_div_scale_f32 v83, vcc, v89, v86, v89
	v_mul_f32_e32 v84, v83, v94
	v_fma_f32 v88, -v87, v84, v83
	v_fmac_f32_e32 v84, v88, v94
	v_fma_f32 v83, -v87, v84, v83
	v_div_fmas_f32 v83, v83, v94, v84
	v_mul_f32_e32 v84, 0xbfb8aa3b, v78
	v_exp_f32_e32 v84, v84
	v_div_fixup_f32 v83, v83, v86, v89
	v_mul_f32_e32 v83, v83, v85
	v_cvt_pk_bf16_f32 v93, v82, v83
	v_add_f32_e32 v84, 1.0, v84
	v_div_scale_f32 v85, s[8:9], v84, v84, v78
	v_rcp_f32_e32 v86, v85
	v_add_u32_e32 v82, 0x4020, v1
	v_mad_i64_i32 v[82:83], s[8:9], v82, s5, v[114:115]
	v_lshl_add_u64 v[82:83], v[82:83], 0, v[116:117]
	global_store_dwordx4 v[82:83], v[90:93], off
	v_fma_f32 v82, -v85, v86, 1.0
	v_mul_f32_e32 v87, 0xbfb8aa3b, v79
	v_fmac_f32_e32 v86, v82, v86
	v_div_scale_f32 v82, vcc, v78, v84, v78
	v_exp_f32_e32 v87, v87
	v_mul_f32_e32 v83, v82, v86
	v_fma_f32 v88, -v85, v83, v82
	v_fmac_f32_e32 v83, v88, v86
	v_fma_f32 v82, -v85, v83, v82
	v_add_f32_e32 v85, 1.0, v87
	v_div_scale_f32 v87, s[8:9], v85, v85, v79
	v_rcp_f32_e32 v88, v87
	v_div_fmas_f32 v82, v82, v86, v83
	v_div_fixup_f32 v78, v82, v84, v78
	v_mul_f32_e32 v74, v78, v74
	v_fma_f32 v78, -v87, v88, 1.0
	v_fmac_f32_e32 v88, v78, v88
	v_div_scale_f32 v78, vcc, v79, v85, v79
	v_mul_f32_e32 v82, v78, v88
	v_fma_f32 v83, -v87, v82, v78
	v_fmac_f32_e32 v82, v83, v88
	v_mul_f32_e32 v83, 0xbfb8aa3b, v80
	v_exp_f32_e32 v83, v83
	v_fma_f32 v78, -v87, v82, v78
	v_div_fmas_f32 v78, v78, v88, v82
	v_div_fixup_f32 v78, v78, v85, v79
	v_add_f32_e32 v82, 1.0, v83
	v_div_scale_f32 v83, s[8:9], v82, v82, v80
	v_rcp_f32_e32 v84, v83
	v_mul_f32_e32 v75, v78, v75
	v_mul_f32_e32 v79, 0xbfb8aa3b, v81
	v_cvt_pk_bf16_f32 v74, v74, v75
	v_fma_f32 v75, -v83, v84, 1.0
	v_exp_f32_e32 v79, v79
	v_fmac_f32_e32 v84, v75, v84
	v_div_scale_f32 v75, vcc, v80, v82, v80
	v_mul_f32_e32 v78, v75, v84
	v_fma_f32 v85, -v83, v78, v75
	v_fmac_f32_e32 v78, v85, v84
	v_add_f32_e32 v79, 1.0, v79
	v_fma_f32 v75, -v83, v78, v75
	v_div_scale_f32 v83, s[8:9], v79, v79, v81
	v_rcp_f32_e32 v85, v83
	v_div_fmas_f32 v75, v75, v84, v78
	v_div_fixup_f32 v75, v75, v82, v80
	v_mul_f32_e32 v75, v75, v76
	v_fma_f32 v76, -v83, v85, 1.0
	v_fmac_f32_e32 v85, v76, v85
	v_div_scale_f32 v76, vcc, v81, v79, v81
	v_mul_f32_e32 v78, v76, v85
	v_fma_f32 v80, -v83, v78, v76
	v_fmac_f32_e32 v78, v80, v85
	v_mul_f32_e32 v80, 0xbfb8aa3b, v70
	v_exp_f32_e32 v80, v80
	v_fma_f32 v76, -v83, v78, v76
	v_div_fmas_f32 v76, v76, v85, v78
	v_div_fixup_f32 v76, v76, v79, v81
	v_add_f32_e32 v78, 1.0, v80
	v_div_scale_f32 v80, s[8:9], v78, v78, v70
	v_rcp_f32_e32 v82, v80
	v_mul_f32_e32 v76, v76, v77
	v_mul_f32_e32 v79, 0xbfb8aa3b, v71
	v_cvt_pk_bf16_f32 v75, v75, v76
	v_fma_f32 v76, -v80, v82, 1.0
	v_exp_f32_e32 v79, v79
	v_fmac_f32_e32 v82, v76, v82
	v_div_scale_f32 v76, vcc, v70, v78, v70
	v_mul_f32_e32 v77, v76, v82
	v_fma_f32 v81, -v80, v77, v76
	v_fmac_f32_e32 v77, v81, v82
	v_add_f32_e32 v79, 1.0, v79
	v_fma_f32 v76, -v80, v77, v76
	v_div_scale_f32 v80, s[8:9], v79, v79, v71
	v_rcp_f32_e32 v81, v80
	v_div_fmas_f32 v76, v76, v82, v77
	v_div_fixup_f32 v70, v76, v78, v70
	v_mul_f32_e32 v66, v70, v66
	v_fma_f32 v70, -v80, v81, 1.0
	v_fmac_f32_e32 v81, v70, v81
	v_div_scale_f32 v70, vcc, v71, v79, v71
	v_mul_f32_e32 v76, v70, v81
	v_fma_f32 v77, -v80, v76, v70
	v_fmac_f32_e32 v76, v77, v81
	v_mul_f32_e32 v77, 0xbfb8aa3b, v72
	v_exp_f32_e32 v77, v77
	v_fma_f32 v70, -v80, v76, v70
	v_div_fmas_f32 v70, v70, v81, v76
	v_div_fixup_f32 v70, v70, v79, v71
	v_add_f32_e32 v77, 1.0, v77
	v_div_scale_f32 v78, s[8:9], v77, v77, v72
	v_rcp_f32_e32 v80, v78
	v_mul_f32_e32 v67, v70, v67
	v_mul_f32_e32 v70, 0xbfb8aa3b, v73
	v_exp_f32_e32 v70, v70
	v_cvt_pk_bf16_f32 v76, v66, v67
	v_fma_f32 v66, -v78, v80, 1.0
	v_fmac_f32_e32 v80, v66, v80
	v_div_scale_f32 v66, vcc, v72, v77, v72
	v_mul_f32_e32 v67, v66, v80
	v_fma_f32 v71, -v78, v67, v66
	v_add_f32_e32 v70, 1.0, v70
	v_fmac_f32_e32 v67, v71, v80
	v_div_scale_f32 v71, s[8:9], v70, v70, v73
	v_fma_f32 v66, -v78, v67, v66
	v_rcp_f32_e32 v78, v71
	v_div_fmas_f32 v66, v66, v80, v67
	v_div_fixup_f32 v66, v66, v77, v72
	v_mul_f32_e32 v66, v66, v68
	v_fma_f32 v67, -v71, v78, 1.0
	v_fmac_f32_e32 v78, v67, v78
	v_div_scale_f32 v67, vcc, v73, v70, v73
	v_mul_f32_e32 v68, v67, v78
	v_fma_f32 v72, -v71, v68, v67
	v_fmac_f32_e32 v68, v72, v78
	v_fma_f32 v67, -v71, v68, v67
	v_div_fmas_f32 v67, v67, v78, v68
	v_div_fixup_f32 v67, v67, v70, v73
	v_mul_f32_e32 v67, v67, v69
	v_cvt_pk_bf16_f32 v77, v66, v67
	v_mul_f32_e32 v66, 0xbfb8aa3b, v62
	v_exp_f32_e32 v68, v66
	v_add_u32_e32 v66, 0x4030, v1
	v_mad_i64_i32 v[66:67], s[8:9], v66, s5, v[114:115]
	v_add_f32_e32 v68, 1.0, v68
	v_div_scale_f32 v69, s[8:9], v68, v68, v62
	v_rcp_f32_e32 v70, v69
	v_lshl_add_u64 v[66:67], v[66:67], 0, v[116:117]
	global_store_dwordx4 v[66:67], v[74:77], off
	v_mul_f32_e32 v72, 0xbfb8aa3b, v63
	v_fma_f32 v67, -v69, v70, 1.0
	v_fmac_f32_e32 v70, v67, v70
	v_div_scale_f32 v67, vcc, v62, v68, v62
	v_exp_f32_e32 v72, v72
	v_mul_f32_e32 v71, v67, v70
	v_fma_f32 v73, -v69, v71, v67
	v_fmac_f32_e32 v71, v73, v70
	v_fma_f32 v67, -v69, v71, v67
	v_add_f32_e32 v69, 1.0, v72
	v_div_scale_f32 v72, s[8:9], v69, v69, v63
	v_rcp_f32_e32 v73, v72
	v_div_fmas_f32 v67, v67, v70, v71
	v_div_fixup_f32 v62, v67, v68, v62
	v_mul_f32_e32 v58, v62, v58
	v_fma_f32 v62, -v72, v73, 1.0
	v_fmac_f32_e32 v73, v62, v73
	v_div_scale_f32 v62, vcc, v63, v69, v63
	v_mul_f32_e32 v67, v62, v73
	v_fma_f32 v68, -v72, v67, v62
	v_fmac_f32_e32 v67, v68, v73
	v_mul_f32_e32 v68, 0xbfb8aa3b, v64
	v_exp_f32_e32 v68, v68
	v_fma_f32 v62, -v72, v67, v62
	v_div_fmas_f32 v62, v62, v73, v67
	v_div_fixup_f32 v62, v62, v69, v63
	v_add_f32_e32 v67, 1.0, v68
	v_div_scale_f32 v68, s[8:9], v67, v67, v64
	v_rcp_f32_e32 v70, v68
	v_mul_f32_e32 v59, v62, v59
	v_mul_f32_e32 v63, 0xbfb8aa3b, v65
	v_cvt_pk_bf16_f32 v58, v58, v59
	v_fma_f32 v59, -v68, v70, 1.0
	v_exp_f32_e32 v63, v63
	v_fmac_f32_e32 v70, v59, v70
	v_div_scale_f32 v59, vcc, v64, v67, v64
	v_mul_f32_e32 v62, v59, v70
	v_fma_f32 v69, -v68, v62, v59
	v_fmac_f32_e32 v62, v69, v70
	v_add_f32_e32 v63, 1.0, v63
	v_fma_f32 v59, -v68, v62, v59
	v_div_scale_f32 v68, s[8:9], v63, v63, v65
	v_rcp_f32_e32 v69, v68
	v_div_fmas_f32 v59, v59, v70, v62
	v_div_fixup_f32 v59, v59, v67, v64
	v_mul_f32_e32 v59, v59, v60
	v_fma_f32 v60, -v68, v69, 1.0
	v_fmac_f32_e32 v69, v60, v69
	v_div_scale_f32 v60, vcc, v65, v63, v65
	v_mul_f32_e32 v62, v60, v69
	v_fma_f32 v64, -v68, v62, v60
	v_fmac_f32_e32 v62, v64, v69
	v_mul_f32_e32 v64, 0xbfb8aa3b, v54
	v_exp_f32_e32 v64, v64
	v_fma_f32 v60, -v68, v62, v60
	v_div_fmas_f32 v60, v60, v69, v62
	v_div_fixup_f32 v60, v60, v63, v65
	v_add_f32_e32 v62, 1.0, v64
	v_div_scale_f32 v64, s[8:9], v62, v62, v54
	v_rcp_f32_e32 v67, v64
	v_mul_f32_e32 v60, v60, v61
	v_mul_f32_e32 v63, 0xbfb8aa3b, v55
	v_cvt_pk_bf16_f32 v59, v59, v60
	v_fma_f32 v60, -v64, v67, 1.0
	v_exp_f32_e32 v63, v63
	v_fmac_f32_e32 v67, v60, v67
	v_div_scale_f32 v60, vcc, v54, v62, v54
	v_mul_f32_e32 v61, v60, v67
	v_fma_f32 v65, -v64, v61, v60
	v_fmac_f32_e32 v61, v65, v67
	v_add_f32_e32 v63, 1.0, v63
	v_fma_f32 v60, -v64, v61, v60
	v_div_scale_f32 v64, s[8:9], v63, v63, v55
	v_rcp_f32_e32 v65, v64
	v_div_fmas_f32 v60, v60, v67, v61
	v_div_fixup_f32 v54, v60, v62, v54
	v_mul_f32_e32 v50, v54, v50
	v_fma_f32 v54, -v64, v65, 1.0
	v_fmac_f32_e32 v65, v54, v65
	v_div_scale_f32 v54, vcc, v55, v63, v55
	v_mul_f32_e32 v60, v54, v65
	v_fma_f32 v61, -v64, v60, v54
	v_fmac_f32_e32 v60, v61, v65
	v_mul_f32_e32 v61, 0xbfb8aa3b, v56
	v_exp_f32_e32 v61, v61
	v_fma_f32 v54, -v64, v60, v54
	v_div_fmas_f32 v54, v54, v65, v60
	v_div_fixup_f32 v54, v54, v63, v55
	v_add_f32_e32 v61, 1.0, v61
	v_div_scale_f32 v62, s[8:9], v61, v61, v56
	v_rcp_f32_e32 v64, v62
	v_mul_f32_e32 v51, v54, v51
	v_mul_f32_e32 v54, 0xbfb8aa3b, v57
	v_exp_f32_e32 v54, v54
	v_cvt_pk_bf16_f32 v60, v50, v51
	v_fma_f32 v50, -v62, v64, 1.0
	v_fmac_f32_e32 v64, v50, v64
	v_div_scale_f32 v50, vcc, v56, v61, v56
	v_mul_f32_e32 v51, v50, v64
	v_fma_f32 v55, -v62, v51, v50
	v_add_f32_e32 v54, 1.0, v54
	v_fmac_f32_e32 v51, v55, v64
	v_div_scale_f32 v55, s[8:9], v54, v54, v57
	v_fma_f32 v50, -v62, v51, v50
	v_rcp_f32_e32 v62, v55
	v_div_fmas_f32 v50, v50, v64, v51
	v_div_fixup_f32 v50, v50, v61, v56
	v_mul_f32_e32 v50, v50, v52
	v_fma_f32 v51, -v55, v62, 1.0
	v_fmac_f32_e32 v62, v51, v62
	v_div_scale_f32 v51, vcc, v57, v54, v57
	v_mul_f32_e32 v52, v51, v62
	v_fma_f32 v56, -v55, v52, v51
	v_fmac_f32_e32 v52, v56, v62
	v_fma_f32 v51, -v55, v52, v51
	v_div_fmas_f32 v51, v51, v62, v52
	v_mul_f32_e32 v52, 0xbfb8aa3b, v46
	v_exp_f32_e32 v52, v52
	v_div_fixup_f32 v51, v51, v54, v57
	v_mul_f32_e32 v51, v51, v53
	v_add_u32_e32 v66, 0x4080, v1
	v_add_f32_e32 v52, 1.0, v52
	v_div_scale_f32 v53, s[8:9], v52, v52, v46
	v_rcp_f32_e32 v54, v53
	v_cvt_pk_bf16_f32 v61, v50, v51
	v_mad_i64_i32 v[50:51], s[8:9], v66, s5, v[114:115]
	v_lshl_add_u64 v[50:51], v[50:51], 0, v[116:117]
	global_store_dwordx4 v[50:51], v[58:61], off
	v_fma_f32 v50, -v53, v54, 1.0
	v_mul_f32_e32 v55, 0xbfb8aa3b, v47
	v_fmac_f32_e32 v54, v50, v54
	v_div_scale_f32 v50, vcc, v46, v52, v46
	v_exp_f32_e32 v55, v55
	v_mul_f32_e32 v51, v50, v54
	v_fma_f32 v56, -v53, v51, v50
	v_fmac_f32_e32 v51, v56, v54
	v_fma_f32 v50, -v53, v51, v50
	v_add_f32_e32 v53, 1.0, v55
	v_div_scale_f32 v55, s[8:9], v53, v53, v47
	v_rcp_f32_e32 v56, v55
	v_div_fmas_f32 v50, v50, v54, v51
	v_div_fixup_f32 v46, v50, v52, v46
	v_mul_f32_e32 v42, v46, v42
	v_fma_f32 v46, -v55, v56, 1.0
	v_fmac_f32_e32 v56, v46, v56
	v_div_scale_f32 v46, vcc, v47, v53, v47
	v_mul_f32_e32 v50, v46, v56
	v_fma_f32 v51, -v55, v50, v46
	v_fmac_f32_e32 v50, v51, v56
	v_mul_f32_e32 v51, 0xbfb8aa3b, v48
	v_exp_f32_e32 v51, v51
	v_fma_f32 v46, -v55, v50, v46
	v_div_fmas_f32 v46, v46, v56, v50
	v_div_fixup_f32 v46, v46, v53, v47
	v_add_f32_e32 v50, 1.0, v51
	v_div_scale_f32 v51, s[8:9], v50, v50, v48
	v_rcp_f32_e32 v52, v51
	v_mul_f32_e32 v43, v46, v43
	v_mul_f32_e32 v47, 0xbfb8aa3b, v49
	v_cvt_pk_bf16_f32 v42, v42, v43
	v_fma_f32 v43, -v51, v52, 1.0
	v_exp_f32_e32 v47, v47
	v_fmac_f32_e32 v52, v43, v52
	v_div_scale_f32 v43, vcc, v48, v50, v48
	v_mul_f32_e32 v46, v43, v52
	v_fma_f32 v53, -v51, v46, v43
	v_fmac_f32_e32 v46, v53, v52
	v_add_f32_e32 v47, 1.0, v47
	v_fma_f32 v43, -v51, v46, v43
	v_div_scale_f32 v51, s[8:9], v47, v47, v49
	v_rcp_f32_e32 v53, v51
	v_div_fmas_f32 v43, v43, v52, v46
	v_div_fixup_f32 v43, v43, v50, v48
	v_mul_f32_e32 v43, v43, v44
	v_fma_f32 v44, -v51, v53, 1.0
	v_fmac_f32_e32 v53, v44, v53
	v_div_scale_f32 v44, vcc, v49, v47, v49
	v_mul_f32_e32 v46, v44, v53
	v_fma_f32 v48, -v51, v46, v44
	v_fmac_f32_e32 v46, v48, v53
	v_mul_f32_e32 v48, 0xbfb8aa3b, v38
	v_exp_f32_e32 v48, v48
	v_fma_f32 v44, -v51, v46, v44
	v_div_fmas_f32 v44, v44, v53, v46
	v_div_fixup_f32 v44, v44, v47, v49
	v_add_f32_e32 v46, 1.0, v48
	v_div_scale_f32 v48, s[8:9], v46, v46, v38
	v_rcp_f32_e32 v50, v48
	v_mul_f32_e32 v44, v44, v45
	v_mul_f32_e32 v47, 0xbfb8aa3b, v39
	v_cvt_pk_bf16_f32 v43, v43, v44
	v_fma_f32 v44, -v48, v50, 1.0
	v_exp_f32_e32 v47, v47
	v_fmac_f32_e32 v50, v44, v50
	v_div_scale_f32 v44, vcc, v38, v46, v38
	v_mul_f32_e32 v45, v44, v50
	v_fma_f32 v49, -v48, v45, v44
	v_fmac_f32_e32 v45, v49, v50
	v_add_f32_e32 v47, 1.0, v47
	v_fma_f32 v44, -v48, v45, v44
	v_div_scale_f32 v48, s[8:9], v47, v47, v39
	v_rcp_f32_e32 v49, v48
	v_div_fmas_f32 v44, v44, v50, v45
	v_div_fixup_f32 v38, v44, v46, v38
	v_mul_f32_e32 v34, v38, v34
	v_fma_f32 v38, -v48, v49, 1.0
	v_fmac_f32_e32 v49, v38, v49
	v_div_scale_f32 v38, vcc, v39, v47, v39
	v_mul_f32_e32 v44, v38, v49
	v_fma_f32 v45, -v48, v44, v38
	v_fmac_f32_e32 v44, v45, v49
	v_mul_f32_e32 v45, 0xbfb8aa3b, v40
	v_exp_f32_e32 v45, v45
	v_fma_f32 v38, -v48, v44, v38
	v_div_fmas_f32 v38, v38, v49, v44
	v_div_fixup_f32 v38, v38, v47, v39
	v_add_f32_e32 v45, 1.0, v45
	v_div_scale_f32 v46, s[8:9], v45, v45, v40
	v_rcp_f32_e32 v48, v46
	v_mul_f32_e32 v35, v38, v35
	v_mul_f32_e32 v38, 0xbfb8aa3b, v41
	v_exp_f32_e32 v38, v38
	v_cvt_pk_bf16_f32 v44, v34, v35
	v_fma_f32 v34, -v46, v48, 1.0
	v_fmac_f32_e32 v48, v34, v48
	v_div_scale_f32 v34, vcc, v40, v45, v40
	v_mul_f32_e32 v35, v34, v48
	v_fma_f32 v39, -v46, v35, v34
	v_add_f32_e32 v38, 1.0, v38
	v_fmac_f32_e32 v35, v39, v48
	v_div_scale_f32 v39, s[8:9], v38, v38, v41
	v_fma_f32 v34, -v46, v35, v34
	v_rcp_f32_e32 v46, v39
	v_div_fmas_f32 v34, v34, v48, v35
	v_div_fixup_f32 v34, v34, v45, v40
	v_mul_f32_e32 v34, v34, v36
	v_fma_f32 v35, -v39, v46, 1.0
	v_fmac_f32_e32 v46, v35, v46
	v_div_scale_f32 v35, vcc, v41, v38, v41
	v_mul_f32_e32 v36, v35, v46
	v_fma_f32 v40, -v39, v36, v35
	v_fmac_f32_e32 v36, v40, v46
	v_fma_f32 v35, -v39, v36, v35
	v_div_fmas_f32 v35, v35, v46, v36
	v_mul_f32_e32 v36, 0xbfb8aa3b, v30
	v_exp_f32_e32 v36, v36
	v_div_fixup_f32 v35, v35, v38, v41
	v_mul_f32_e32 v35, v35, v37
	v_cvt_pk_bf16_f32 v45, v34, v35
	v_add_f32_e32 v36, 1.0, v36
	v_div_scale_f32 v37, s[8:9], v36, v36, v30
	v_rcp_f32_e32 v38, v37
	v_add_u32_e32 v34, 0x4090, v1
	v_mad_i64_i32 v[34:35], s[8:9], v34, s5, v[114:115]
	v_lshl_add_u64 v[34:35], v[34:35], 0, v[116:117]
	global_store_dwordx4 v[34:35], v[42:45], off
	v_fma_f32 v34, -v37, v38, 1.0
	v_mul_f32_e32 v39, 0xbfb8aa3b, v31
	v_fmac_f32_e32 v38, v34, v38
	v_div_scale_f32 v34, vcc, v30, v36, v30
	v_exp_f32_e32 v39, v39
	v_mul_f32_e32 v35, v34, v38
	v_fma_f32 v40, -v37, v35, v34
	v_fmac_f32_e32 v35, v40, v38
	v_fma_f32 v34, -v37, v35, v34
	v_add_f32_e32 v37, 1.0, v39
	v_div_scale_f32 v39, s[8:9], v37, v37, v31
	v_rcp_f32_e32 v40, v39
	v_div_fmas_f32 v34, v34, v38, v35
	v_div_fixup_f32 v30, v34, v36, v30
	v_mul_f32_e32 v26, v30, v26
	v_fma_f32 v30, -v39, v40, 1.0
	v_fmac_f32_e32 v40, v30, v40
	v_div_scale_f32 v30, vcc, v31, v37, v31
	v_mul_f32_e32 v34, v30, v40
	v_fma_f32 v35, -v39, v34, v30
	v_fmac_f32_e32 v34, v35, v40
	v_mul_f32_e32 v35, 0xbfb8aa3b, v32
	v_exp_f32_e32 v35, v35
	v_fma_f32 v30, -v39, v34, v30
	v_div_fmas_f32 v30, v30, v40, v34
	v_div_fixup_f32 v30, v30, v37, v31
	v_add_f32_e32 v34, 1.0, v35
	v_div_scale_f32 v35, s[8:9], v34, v34, v32
	v_rcp_f32_e32 v36, v35
	v_mul_f32_e32 v27, v30, v27
	v_mul_f32_e32 v31, 0xbfb8aa3b, v33
	v_cvt_pk_bf16_f32 v26, v26, v27
	v_fma_f32 v27, -v35, v36, 1.0
	v_exp_f32_e32 v31, v31
	v_fmac_f32_e32 v36, v27, v36
	v_div_scale_f32 v27, vcc, v32, v34, v32
	v_mul_f32_e32 v30, v27, v36
	v_fma_f32 v37, -v35, v30, v27
	v_fmac_f32_e32 v30, v37, v36
	v_add_f32_e32 v31, 1.0, v31
	v_fma_f32 v27, -v35, v30, v27
	v_div_scale_f32 v35, s[8:9], v31, v31, v33
	v_rcp_f32_e32 v37, v35
	v_div_fmas_f32 v27, v27, v36, v30
	v_div_fixup_f32 v27, v27, v34, v32
	v_mul_f32_e32 v27, v27, v28
	v_fma_f32 v28, -v35, v37, 1.0
	v_fmac_f32_e32 v37, v28, v37
	v_div_scale_f32 v28, vcc, v33, v31, v33
	v_mul_f32_e32 v30, v28, v37
	v_fma_f32 v32, -v35, v30, v28
	v_fmac_f32_e32 v30, v32, v37
	v_mul_f32_e32 v32, 0xbfb8aa3b, v22
	v_exp_f32_e32 v32, v32
	v_fma_f32 v28, -v35, v30, v28
	v_div_fmas_f32 v28, v28, v37, v30
	v_div_fixup_f32 v28, v28, v31, v33
	v_add_f32_e32 v30, 1.0, v32
	v_div_scale_f32 v32, s[8:9], v30, v30, v22
	v_rcp_f32_e32 v34, v32
	v_mul_f32_e32 v28, v28, v29
	v_mul_f32_e32 v31, 0xbfb8aa3b, v23
	v_cvt_pk_bf16_f32 v27, v27, v28
	v_fma_f32 v28, -v32, v34, 1.0
	v_exp_f32_e32 v31, v31
	v_fmac_f32_e32 v34, v28, v34
	v_div_scale_f32 v28, vcc, v22, v30, v22
	v_mul_f32_e32 v29, v28, v34
	v_fma_f32 v33, -v32, v29, v28
	v_fmac_f32_e32 v29, v33, v34
	v_add_f32_e32 v31, 1.0, v31
	v_fma_f32 v28, -v32, v29, v28
	v_div_scale_f32 v32, s[8:9], v31, v31, v23
	v_rcp_f32_e32 v33, v32
	v_div_fmas_f32 v28, v28, v34, v29
	v_div_fixup_f32 v22, v28, v30, v22
	v_mul_f32_e32 v18, v22, v18
	v_fma_f32 v22, -v32, v33, 1.0
	v_fmac_f32_e32 v33, v22, v33
	v_div_scale_f32 v22, vcc, v23, v31, v23
	v_mul_f32_e32 v28, v22, v33
	v_fma_f32 v29, -v32, v28, v22
	v_fmac_f32_e32 v28, v29, v33
	v_mul_f32_e32 v29, 0xbfb8aa3b, v24
	v_exp_f32_e32 v29, v29
	v_fma_f32 v22, -v32, v28, v22
	v_div_fmas_f32 v22, v22, v33, v28
	v_div_fixup_f32 v22, v22, v31, v23
	v_add_f32_e32 v29, 1.0, v29
	v_div_scale_f32 v30, s[8:9], v29, v29, v24
	v_rcp_f32_e32 v32, v30
	v_mul_f32_e32 v19, v22, v19
	v_mul_f32_e32 v22, 0xbfb8aa3b, v25
	v_exp_f32_e32 v22, v22
	v_cvt_pk_bf16_f32 v28, v18, v19
	v_fma_f32 v18, -v30, v32, 1.0
	v_fmac_f32_e32 v32, v18, v32
	v_div_scale_f32 v18, vcc, v24, v29, v24
	v_mul_f32_e32 v19, v18, v32
	v_fma_f32 v23, -v30, v19, v18
	v_add_f32_e32 v22, 1.0, v22
	v_fmac_f32_e32 v19, v23, v32
	v_div_scale_f32 v23, s[8:9], v22, v22, v25
	v_fma_f32 v18, -v30, v19, v18
	v_rcp_f32_e32 v30, v23
	v_div_fmas_f32 v18, v18, v32, v19
	v_div_fixup_f32 v18, v18, v29, v24
	v_mul_f32_e32 v18, v18, v20
	v_fma_f32 v19, -v23, v30, 1.0
	v_fmac_f32_e32 v30, v19, v30
	v_div_scale_f32 v19, vcc, v25, v22, v25
	v_mul_f32_e32 v20, v19, v30
	v_fma_f32 v24, -v23, v20, v19
	v_fmac_f32_e32 v20, v24, v30
	v_fma_f32 v19, -v23, v20, v19
	v_div_fmas_f32 v19, v19, v30, v20
	v_mul_f32_e32 v20, 0xbfb8aa3b, v14
	v_exp_f32_e32 v20, v20
	v_div_fixup_f32 v19, v19, v22, v25
	v_mul_f32_e32 v19, v19, v21
	v_cvt_pk_bf16_f32 v29, v18, v19
	v_add_f32_e32 v20, 1.0, v20
	v_div_scale_f32 v21, s[8:9], v20, v20, v14
	v_rcp_f32_e32 v22, v21
	v_add_u32_e32 v18, 0x40a0, v1
	v_mad_i64_i32 v[18:19], s[8:9], v18, s5, v[114:115]
	v_lshl_add_u64 v[18:19], v[18:19], 0, v[116:117]
	global_store_dwordx4 v[18:19], v[26:29], off
	v_fma_f32 v18, -v21, v22, 1.0
	v_mul_f32_e32 v23, 0xbfb8aa3b, v15
	v_fmac_f32_e32 v22, v18, v22
	v_div_scale_f32 v18, vcc, v14, v20, v14
	v_exp_f32_e32 v23, v23
	v_mul_f32_e32 v19, v18, v22
	v_fma_f32 v24, -v21, v19, v18
	v_fmac_f32_e32 v19, v24, v22
	v_fma_f32 v18, -v21, v19, v18
	v_add_f32_e32 v21, 1.0, v23
	v_div_scale_f32 v23, s[8:9], v21, v21, v15
	v_rcp_f32_e32 v24, v23
	v_div_fmas_f32 v18, v18, v22, v19
	v_div_fixup_f32 v14, v18, v20, v14
	v_mul_f32_e32 v10, v14, v10
	v_fma_f32 v14, -v23, v24, 1.0
	v_fmac_f32_e32 v24, v14, v24
	v_div_scale_f32 v14, vcc, v15, v21, v15
	v_mul_f32_e32 v18, v14, v24
	v_fma_f32 v19, -v23, v18, v14
	v_fmac_f32_e32 v18, v19, v24
	v_mul_f32_e32 v19, 0xbfb8aa3b, v16
	v_exp_f32_e32 v19, v19
	v_fma_f32 v14, -v23, v18, v14
	v_div_fmas_f32 v14, v14, v24, v18
	v_div_fixup_f32 v14, v14, v21, v15
	v_add_f32_e32 v18, 1.0, v19
	v_div_scale_f32 v19, s[8:9], v18, v18, v16
	v_rcp_f32_e32 v20, v19
	v_mul_f32_e32 v11, v14, v11
	v_mul_f32_e32 v15, 0xbfb8aa3b, v17
	v_cvt_pk_bf16_f32 v10, v10, v11
	v_fma_f32 v11, -v19, v20, 1.0
	v_exp_f32_e32 v15, v15
	v_fmac_f32_e32 v20, v11, v20
	v_div_scale_f32 v11, vcc, v16, v18, v16
	v_mul_f32_e32 v14, v11, v20
	v_fma_f32 v21, -v19, v14, v11
	v_fmac_f32_e32 v14, v21, v20
	v_add_f32_e32 v15, 1.0, v15
	v_fma_f32 v11, -v19, v14, v11
	v_div_scale_f32 v19, s[8:9], v15, v15, v17
	v_rcp_f32_e32 v21, v19
	v_div_fmas_f32 v11, v11, v20, v14
	v_div_fixup_f32 v11, v11, v18, v16
	v_mul_f32_e32 v11, v11, v12
	v_fma_f32 v12, -v19, v21, 1.0
	v_fmac_f32_e32 v21, v12, v21
	v_div_scale_f32 v12, vcc, v17, v15, v17
	v_mul_f32_e32 v14, v12, v21
	v_fma_f32 v16, -v19, v14, v12
	v_fmac_f32_e32 v14, v16, v21
	v_mul_f32_e32 v16, 0xbfb8aa3b, v6
	v_exp_f32_e32 v16, v16
	v_fma_f32 v12, -v19, v14, v12
	v_div_fmas_f32 v12, v12, v21, v14
	v_div_fixup_f32 v12, v12, v15, v17
	v_add_f32_e32 v14, 1.0, v16
	v_div_scale_f32 v16, s[8:9], v14, v14, v6
	v_rcp_f32_e32 v18, v16
	v_mul_f32_e32 v12, v12, v13
	v_mul_f32_e32 v15, 0xbfb8aa3b, v7
	v_cvt_pk_bf16_f32 v11, v11, v12
	v_fma_f32 v12, -v16, v18, 1.0
	v_exp_f32_e32 v15, v15
	v_fmac_f32_e32 v18, v12, v18
	v_div_scale_f32 v12, vcc, v6, v14, v6
	v_mul_f32_e32 v13, v12, v18
	v_fma_f32 v17, -v16, v13, v12
	v_fmac_f32_e32 v13, v17, v18
	v_add_f32_e32 v15, 1.0, v15
	v_fma_f32 v12, -v16, v13, v12
	v_div_scale_f32 v16, s[8:9], v15, v15, v7
	v_rcp_f32_e32 v17, v16
	v_div_fmas_f32 v12, v12, v18, v13
	v_div_fixup_f32 v6, v12, v14, v6
	v_mul_f32_e32 v2, v6, v2
	v_fma_f32 v6, -v16, v17, 1.0
	v_fmac_f32_e32 v17, v6, v17
	v_div_scale_f32 v6, vcc, v7, v15, v7
	v_mul_f32_e32 v12, v6, v17
	v_fma_f32 v13, -v16, v12, v6
	v_fmac_f32_e32 v12, v13, v17
	v_mul_f32_e32 v13, 0xbfb8aa3b, v8
	v_exp_f32_e32 v13, v13
	v_fma_f32 v6, -v16, v12, v6
	v_div_fmas_f32 v6, v6, v17, v12
	v_div_fixup_f32 v6, v6, v15, v7
	v_add_f32_e32 v13, 1.0, v13
	v_div_scale_f32 v14, s[8:9], v13, v13, v8
	v_rcp_f32_e32 v16, v14
	v_mul_f32_e32 v3, v6, v3
	v_mul_f32_e32 v6, 0xbfb8aa3b, v9
	v_exp_f32_e32 v6, v6
	v_cvt_pk_bf16_f32 v12, v2, v3
	v_fma_f32 v2, -v14, v16, 1.0
	v_fmac_f32_e32 v16, v2, v16
	v_div_scale_f32 v2, vcc, v8, v13, v8
	v_mul_f32_e32 v3, v2, v16
	v_fma_f32 v7, -v14, v3, v2
	v_add_f32_e32 v6, 1.0, v6
	v_fmac_f32_e32 v3, v7, v16
	v_div_scale_f32 v7, s[8:9], v6, v6, v9
	v_fma_f32 v2, -v14, v3, v2
	v_rcp_f32_e32 v14, v7
	v_div_fmas_f32 v2, v2, v16, v3
	v_div_fixup_f32 v2, v2, v13, v8
	v_mul_f32_e32 v2, v2, v4
	v_fma_f32 v3, -v7, v14, 1.0
	v_fmac_f32_e32 v14, v3, v14
	v_div_scale_f32 v3, vcc, v9, v6, v9
	v_mul_f32_e32 v4, v3, v14
	v_fma_f32 v8, -v7, v4, v3
	v_fmac_f32_e32 v4, v8, v14
	v_fma_f32 v3, -v7, v4, v3
	v_div_fmas_f32 v3, v3, v14, v4
	v_div_fixup_f32 v3, v3, v6, v9
	v_mul_f32_e32 v3, v3, v5
	v_add_u32_e32 v1, 0x40b0, v1
	v_cvt_pk_bf16_f32 v13, v2, v3
	v_mad_i64_i32 v[2:3], s[8:9], v1, s5, v[114:115]
	v_lshl_add_u64 v[2:3], v[2:3], 0, v[116:117]
	global_store_dwordx4 v[2:3], v[10:13], off
	s_waitcnt vmcnt(0)
	s_barrier
	s_waitcnt vmcnt(0)
	s_waitcnt vmcnt(0) lgkmcnt(0)
	s_barrier
	s_mov_b64 s[8:9], exec
	v_readlane_b32 s10, v228, 2
	v_readlane_b32 s11, v228, 3
	s_and_b64 s[10:11], s[8:9], s[10:11]
	s_mov_b64 exec, s[10:11]
	s_cbranch_execz .LBB0_3407
	s_mov_b64 s[10:11], exec
	v_mbcnt_lo_u32_b32 v1, s10, 0
	buffer_wbl2 sc1
	s_waitcnt vmcnt(0)
	v_mbcnt_hi_u32_b32 v1, s11, v1
	v_cmp_eq_u32_e32 vcc, 0, v1
	s_and_b64 s[20:21], exec, vcc
	s_mov_b64 exec, s[20:21]
	s_cbranch_execz .LBB0_3407
	s_bcnt1_i32_b64 s5, s[10:11]
	v_mov_b32_e32 v1, 0
	v_mov_b32_e32 v2, s5
	global_atomic_add v1, v2, s[6:7]

.LBB0_3423:
	s_add_u32 s6, s38, 0x7800000
	s_addc_u32 s7, s39, 0
	s_lshl_b32 s9, s13, 8
	s_add_i32 s8, s5, 0x4000
	v_lshl_or_b32 v131, v131, 2, s9
	v_or_b32_e32 v134, s36, v131
	v_or_b32_e32 v138, s8, v1
	s_movk_i32 s11, 0x4080
	s_movk_i32 s20, 0x4000
	s_ashr_i32 s10, s8, 13
	v_cmp_gt_i32_e32 vcc, s11, v138
	v_or_b32_e32 v136, 16, v134
	s_and_saveexec_b64 s[8:9], vcc
	s_cbranch_execz .LBB0_3425
	v_cmp_gt_i32_e32 vcc, s20, v138
	v_readlane_b32 s20, v228, 17
	v_add_u32_e32 v131, 0xffffc002, v138
	v_mov_b32_e32 v133, s10
	v_readlane_b32 s21, v228, 18
	v_cndmask_b32_e32 v131, v131, v133, vcc
	s_mov_b32 s13, 0x9000
	v_mov_b64_e32 v[140:141], s[20:21]
	v_mad_i64_i32 v[140:141], s[20:21], v131, s13, v[140:141]
	s_mov_b64 s[20:21], 0x2000
	v_ashrrev_i32_e32 v139, 31, v138
	v_lshl_add_u64 v[152:153], v[140:141], 0, s[20:21]
	v_lshlrev_b64 v[140:141], 12, v[138:139]
	v_add_u32_e32 v154, 0xffffc000, v138
	v_mov_b32_e32 v155, 0
	v_lshl_add_u64 v[148:149], s[6:7], 0, v[140:141]
	v_lshlrev_b64 v[140:141], 12, v[154:155]
	v_mov_b32_e32 v135, v155
	v_lshl_add_u64 v[140:141], s[14:15], 0, v[140:141]
	v_lshlrev_b64 v[150:151], 2, v[134:135]
	v_cndmask_b32_e32 v145, v141, v149, vcc
	v_cndmask_b32_e32 v144, v140, v148, vcc
	v_lshl_add_u64 v[140:141], v[152:153], 0, v[150:151]
	global_load_dwordx4 v[140:143], v[140:141], off
	v_lshl_add_u64 v[156:157], v[144:145], 0, v[150:151]
	global_load_dwordx4 v[144:147], v[156:157], off
	v_mov_b32_e32 v137, v155
	v_lshl_add_u64 v[158:159], v[148:149], 0, v[150:151]
	v_lshl_add_u64 v[148:149], v[136:137], 2, v[152:153]
	global_load_dwordx4 v[148:151], v[148:149], off
	v_or_b32_e32 v154, 0x80, v134
	s_waitcnt vmcnt(0) lgkmcnt(0)
	v_pk_mul_f32 v[128:129], v[128:129], v[142:143]
	v_pk_mul_f32 v[126:127], v[126:127], v[140:141]
	v_pk_fma_f32 v[128:129], v[128:129], 0.5, v[146:147] op_sel_hi:[1,0,1]
	v_pk_fma_f32 v[126:127], v[126:127], 0.5, v[144:145] op_sel_hi:[1,0,1]
	global_store_dwordx4 v[158:159], v[126:129], off
	global_load_dwordx4 v[126:129], v[156:157], off offset:64
	v_pk_mul_f32 v[124:125], v[124:125], v[150:151]
	v_pk_mul_f32 v[122:123], v[122:123], v[148:149]
	v_lshl_add_u64 v[140:141], v[154:155], 2, v[152:153]
	global_load_dwordx4 v[140:143], v[140:141], off
	v_or_b32_e32 v154, 0x90, v134
	s_waitcnt vmcnt(0) lgkmcnt(0)
	v_pk_fma_f32 v[124:125], v[124:125], 0.5, v[128:129] op_sel_hi:[1,0,1]
	v_pk_fma_f32 v[122:123], v[122:123], 0.5, v[126:127] op_sel_hi:[1,0,1]
	global_store_dwordx4 v[158:159], v[122:125], off offset:64
	global_load_dwordx4 v[122:125], v[156:157], off offset:512
	v_lshl_add_u64 v[126:127], v[154:155], 2, v[152:153]
	global_load_dwordx4 v[126:129], v[126:127], off
	v_pk_mul_f32 v[120:121], v[120:121], v[142:143]
	v_pk_mul_f32 v[118:119], v[118:119], v[140:141]
	s_waitcnt vmcnt(0) lgkmcnt(0)
	v_pk_fma_f32 v[120:121], v[120:121], 0.5, v[124:125] op_sel_hi:[1,0,1]
	v_pk_fma_f32 v[118:119], v[118:119], 0.5, v[122:123] op_sel_hi:[1,0,1]
	global_store_dwordx4 v[158:159], v[118:121], off offset:512
	global_load_dwordx4 v[118:121], v[156:157], off offset:576
	v_pk_mul_f32 v[116:117], v[116:117], v[128:129]
	v_pk_mul_f32 v[114:115], v[114:115], v[126:127]
	s_waitcnt vmcnt(0) lgkmcnt(0)
	v_pk_fma_f32 v[116:117], v[116:117], 0.5, v[120:121] op_sel_hi:[1,0,1]
	v_pk_fma_f32 v[114:115], v[114:115], 0.5, v[118:119] op_sel_hi:[1,0,1]
	global_store_dwordx4 v[158:159], v[114:117], off offset:576
.LBB0_3425:
	s_or_b64 exec, exec, s[8:9]
	s_nop 0
	v_or_b32_e32 v114, 16, v138
	v_cmp_gt_i32_e32 vcc, s11, v114
	s_and_saveexec_b64 s[8:9], vcc
	s_cbranch_execz .LBB0_3427
	s_movk_i32 s11, 0x4000
	v_readlane_b32 s20, v228, 17
	v_add_u32_e32 v115, 0xffffc012, v138
	v_mov_b32_e32 v116, s10
	v_cmp_gt_i32_e32 vcc, s11, v114
	v_readlane_b32 s21, v228, 18
	s_mov_b32 s11, 0x9000
	v_cndmask_b32_e32 v115, v115, v116, vcc
	v_mov_b64_e32 v[116:117], s[20:21]
	v_mad_i64_i32 v[116:117], s[20:21], v115, s11, v[116:117]
	v_ashrrev_i32_e32 v115, 31, v114
	v_lshlrev_b64 v[114:115], 12, v[114:115]
	v_add_u32_e32 v128, 0xffffc010, v138
	v_mov_b32_e32 v129, 0
	s_mov_b64 s[20:21], 0x2000
	v_lshl_add_u64 v[122:123], s[6:7], 0, v[114:115]
	v_lshlrev_b64 v[114:115], 12, v[128:129]
	v_mov_b32_e32 v135, v129
	v_lshl_add_u64 v[126:127], v[116:117], 0, s[20:21]
	v_lshl_add_u64 v[114:115], s[14:15], 0, v[114:115]
	v_lshlrev_b64 v[124:125], 2, v[134:135]
	v_cndmask_b32_e32 v119, v115, v123, vcc
	v_cndmask_b32_e32 v118, v114, v122, vcc
	v_lshl_add_u64 v[114:115], v[126:127], 0, v[124:125]
	global_load_dwordx4 v[114:117], v[114:115], off
	v_lshl_add_u64 v[140:141], v[118:119], 0, v[124:125]
	global_load_dwordx4 v[118:121], v[140:141], off
	v_mov_b32_e32 v137, v129
	v_lshl_add_u64 v[142:143], v[122:123], 0, v[124:125]
	v_lshl_add_u64 v[122:123], v[136:137], 2, v[126:127]
	global_load_dwordx4 v[122:125], v[122:123], off
	v_or_b32_e32 v128, 0x80, v134
	s_waitcnt vmcnt(0) lgkmcnt(0)
	v_pk_mul_f32 v[112:113], v[112:113], v[116:117]
	v_pk_mul_f32 v[110:111], v[110:111], v[114:115]
	v_pk_fma_f32 v[112:113], v[112:113], 0.5, v[120:121] op_sel_hi:[1,0,1]
	v_pk_fma_f32 v[110:111], v[110:111], 0.5, v[118:119] op_sel_hi:[1,0,1]
	global_store_dwordx4 v[142:143], v[110:113], off
	global_load_dwordx4 v[110:113], v[140:141], off offset:64
	v_pk_mul_f32 v[108:109], v[108:109], v[124:125]
	v_pk_mul_f32 v[106:107], v[106:107], v[122:123]
	v_lshl_add_u64 v[114:115], v[128:129], 2, v[126:127]
	global_load_dwordx4 v[114:117], v[114:115], off
	v_or_b32_e32 v128, 0x90, v134
	s_waitcnt vmcnt(0) lgkmcnt(0)
	v_pk_fma_f32 v[108:109], v[108:109], 0.5, v[112:113] op_sel_hi:[1,0,1]
	v_pk_fma_f32 v[106:107], v[106:107], 0.5, v[110:111] op_sel_hi:[1,0,1]
	global_store_dwordx4 v[142:143], v[106:109], off offset:64
	global_load_dwordx4 v[106:109], v[140:141], off offset:512
	v_lshl_add_u64 v[110:111], v[128:129], 2, v[126:127]
	global_load_dwordx4 v[110:113], v[110:111], off
	v_pk_mul_f32 v[104:105], v[104:105], v[116:117]
	v_pk_mul_f32 v[102:103], v[102:103], v[114:115]
	s_waitcnt vmcnt(0) lgkmcnt(0)
	v_pk_fma_f32 v[104:105], v[104:105], 0.5, v[108:109] op_sel_hi:[1,0,1]
	v_pk_fma_f32 v[102:103], v[102:103], 0.5, v[106:107] op_sel_hi:[1,0,1]
	global_store_dwordx4 v[142:143], v[102:105], off offset:512
	global_load_dwordx4 v[102:105], v[140:141], off offset:576
	v_pk_mul_f32 v[100:101], v[100:101], v[112:113]
	v_pk_mul_f32 v[98:99], v[98:99], v[110:111]
	s_waitcnt vmcnt(0) lgkmcnt(0)
	v_pk_fma_f32 v[100:101], v[100:101], 0.5, v[104:105] op_sel_hi:[1,0,1]
	v_pk_fma_f32 v[98:99], v[98:99], 0.5, v[102:103] op_sel_hi:[1,0,1]
	global_store_dwordx4 v[142:143], v[98:101], off offset:576
.LBB0_3427:
	s_or_b64 exec, exec, s[8:9]
	s_nop 0
	v_or_b32_e32 v98, 32, v138
	s_movk_i32 s11, 0x4080
	v_cmp_gt_i32_e32 vcc, s11, v98
	s_and_saveexec_b64 s[8:9], vcc
	s_cbranch_execz .LBB0_3429
	s_movk_i32 s13, 0x4000
	v_readlane_b32 s20, v228, 17
	v_add_u32_e32 v99, 0xffffc022, v138
	v_mov_b32_e32 v100, s10
	v_cmp_gt_i32_e32 vcc, s13, v98
	v_readlane_b32 s21, v228, 18
	s_mov_b32 s13, 0x9000
	v_cndmask_b32_e32 v99, v99, v100, vcc
	v_mov_b64_e32 v[100:101], s[20:21]
	v_mad_i64_i32 v[100:101], s[20:21], v99, s13, v[100:101]
	v_ashrrev_i32_e32 v99, 31, v98
	v_lshlrev_b64 v[98:99], 12, v[98:99]
	v_add_u32_e32 v112, 0xffffc020, v138
	v_mov_b32_e32 v113, 0
	s_mov_b64 s[20:21], 0x2000
	v_lshl_add_u64 v[106:107], s[6:7], 0, v[98:99]
	v_lshlrev_b64 v[98:99], 12, v[112:113]
	v_mov_b32_e32 v135, v113
	v_lshl_add_u64 v[110:111], v[100:101], 0, s[20:21]
	v_lshl_add_u64 v[98:99], s[14:15], 0, v[98:99]
	v_lshlrev_b64 v[108:109], 2, v[134:135]
	v_cndmask_b32_e32 v103, v99, v107, vcc
	v_cndmask_b32_e32 v102, v98, v106, vcc
	v_lshl_add_u64 v[98:99], v[110:111], 0, v[108:109]
	global_load_dwordx4 v[98:101], v[98:99], off
	v_lshl_add_u64 v[114:115], v[102:103], 0, v[108:109]
	global_load_dwordx4 v[102:105], v[114:115], off
	v_mov_b32_e32 v137, v113
	v_lshl_add_u64 v[116:117], v[106:107], 0, v[108:109]
	v_lshl_add_u64 v[106:107], v[136:137], 2, v[110:111]
	global_load_dwordx4 v[106:109], v[106:107], off
	v_or_b32_e32 v112, 0x80, v134
	s_waitcnt vmcnt(0) lgkmcnt(0)
	v_pk_mul_f32 v[96:97], v[96:97], v[100:101]
	v_pk_mul_f32 v[94:95], v[94:95], v[98:99]
	v_pk_fma_f32 v[96:97], v[96:97], 0.5, v[104:105] op_sel_hi:[1,0,1]
	v_pk_fma_f32 v[94:95], v[94:95], 0.5, v[102:103] op_sel_hi:[1,0,1]
	global_store_dwordx4 v[116:117], v[94:97], off
	global_load_dwordx4 v[94:97], v[114:115], off offset:64
	v_pk_mul_f32 v[92:93], v[92:93], v[108:109]
	v_pk_mul_f32 v[90:91], v[90:91], v[106:107]
	v_lshl_add_u64 v[98:99], v[112:113], 2, v[110:111]
	global_load_dwordx4 v[98:101], v[98:99], off
	v_or_b32_e32 v112, 0x90, v134
	s_waitcnt vmcnt(0) lgkmcnt(0)
	v_pk_fma_f32 v[92:93], v[92:93], 0.5, v[96:97] op_sel_hi:[1,0,1]
	v_pk_fma_f32 v[90:91], v[90:91], 0.5, v[94:95] op_sel_hi:[1,0,1]
	global_store_dwordx4 v[116:117], v[90:93], off offset:64
	global_load_dwordx4 v[90:93], v[114:115], off offset:512
	v_lshl_add_u64 v[94:95], v[112:113], 2, v[110:111]
	global_load_dwordx4 v[94:97], v[94:95], off
	v_pk_mul_f32 v[88:89], v[88:89], v[100:101]
	v_pk_mul_f32 v[86:87], v[86:87], v[98:99]
	s_waitcnt vmcnt(0) lgkmcnt(0)
	v_pk_fma_f32 v[88:89], v[88:89], 0.5, v[92:93] op_sel_hi:[1,0,1]
	v_pk_fma_f32 v[86:87], v[86:87], 0.5, v[90:91] op_sel_hi:[1,0,1]
	global_store_dwordx4 v[116:117], v[86:89], off offset:512
	global_load_dwordx4 v[86:89], v[114:115], off offset:576
	v_pk_mul_f32 v[84:85], v[84:85], v[96:97]
	v_pk_mul_f32 v[82:83], v[82:83], v[94:95]
	s_waitcnt vmcnt(0) lgkmcnt(0)
	v_pk_fma_f32 v[84:85], v[84:85], 0.5, v[88:89] op_sel_hi:[1,0,1]
	v_pk_fma_f32 v[82:83], v[82:83], 0.5, v[86:87] op_sel_hi:[1,0,1]
	global_store_dwordx4 v[116:117], v[82:85], off offset:576
.LBB0_3429:
	s_or_b64 exec, exec, s[8:9]
	s_nop 0
	v_or_b32_e32 v82, 48, v138
	v_cmp_gt_i32_e32 vcc, s11, v82
	s_and_saveexec_b64 s[8:9], vcc
	s_cbranch_execz .LBB0_3431
	s_movk_i32 s11, 0x4000
	v_readlane_b32 s20, v228, 17
	v_add_u32_e32 v83, 0xffffc032, v138
	v_mov_b32_e32 v84, s10
	v_cmp_gt_i32_e32 vcc, s11, v82
	v_readlane_b32 s21, v228, 18
	s_mov_b32 s10, 0x9000
	v_cndmask_b32_e32 v83, v83, v84, vcc
	v_mov_b64_e32 v[84:85], s[20:21]
	v_mad_i64_i32 v[84:85], s[10:11], v83, s10, v[84:85]
	v_ashrrev_i32_e32 v83, 31, v82
	v_lshlrev_b64 v[82:83], 12, v[82:83]
	v_add_u32_e32 v96, 0xffffc030, v138
	v_mov_b32_e32 v97, 0
	s_mov_b64 s[10:11], 0x2000
	v_lshl_add_u64 v[90:91], s[6:7], 0, v[82:83]
	v_lshlrev_b64 v[82:83], 12, v[96:97]
	v_mov_b32_e32 v135, v97
	v_lshl_add_u64 v[94:95], v[84:85], 0, s[10:11]
	v_lshl_add_u64 v[82:83], s[14:15], 0, v[82:83]
	v_lshlrev_b64 v[92:93], 2, v[134:135]
	v_cndmask_b32_e32 v87, v83, v91, vcc
	v_cndmask_b32_e32 v86, v82, v90, vcc
	v_lshl_add_u64 v[82:83], v[94:95], 0, v[92:93]
	global_load_dwordx4 v[82:85], v[82:83], off
	v_lshl_add_u64 v[98:99], v[86:87], 0, v[92:93]
	global_load_dwordx4 v[86:89], v[98:99], off
	v_mov_b32_e32 v137, v97
	v_lshl_add_u64 v[100:101], v[90:91], 0, v[92:93]
	v_lshl_add_u64 v[90:91], v[136:137], 2, v[94:95]
	global_load_dwordx4 v[90:93], v[90:91], off
	v_or_b32_e32 v96, 0x80, v134
	s_waitcnt vmcnt(0) lgkmcnt(0)
	v_pk_mul_f32 v[80:81], v[80:81], v[84:85]
	v_pk_mul_f32 v[78:79], v[78:79], v[82:83]
	v_pk_fma_f32 v[80:81], v[80:81], 0.5, v[88:89] op_sel_hi:[1,0,1]
	v_pk_fma_f32 v[78:79], v[78:79], 0.5, v[86:87] op_sel_hi:[1,0,1]
	global_store_dwordx4 v[100:101], v[78:81], off
	global_load_dwordx4 v[78:81], v[98:99], off offset:64
	v_pk_mul_f32 v[76:77], v[76:77], v[92:93]
	v_pk_mul_f32 v[74:75], v[74:75], v[90:91]
	v_lshl_add_u64 v[82:83], v[96:97], 2, v[94:95]
	global_load_dwordx4 v[82:85], v[82:83], off
	v_or_b32_e32 v96, 0x90, v134
	s_waitcnt vmcnt(0) lgkmcnt(0)
	v_pk_fma_f32 v[76:77], v[76:77], 0.5, v[80:81] op_sel_hi:[1,0,1]
	v_pk_fma_f32 v[74:75], v[74:75], 0.5, v[78:79] op_sel_hi:[1,0,1]
	global_store_dwordx4 v[100:101], v[74:77], off offset:64
	global_load_dwordx4 v[74:77], v[98:99], off offset:512
	v_lshl_add_u64 v[78:79], v[96:97], 2, v[94:95]
	global_load_dwordx4 v[78:81], v[78:79], off
	v_pk_mul_f32 v[72:73], v[72:73], v[84:85]
	v_pk_mul_f32 v[70:71], v[70:71], v[82:83]
	s_waitcnt vmcnt(0) lgkmcnt(0)
	v_pk_fma_f32 v[72:73], v[72:73], 0.5, v[76:77] op_sel_hi:[1,0,1]
	v_pk_fma_f32 v[70:71], v[70:71], 0.5, v[74:75] op_sel_hi:[1,0,1]
	global_store_dwordx4 v[100:101], v[70:73], off offset:512
	global_load_dwordx4 v[70:73], v[98:99], off offset:576
	v_pk_mul_f32 v[68:69], v[68:69], v[80:81]
	v_pk_mul_f32 v[66:67], v[66:67], v[78:79]
	s_waitcnt vmcnt(0) lgkmcnt(0)
	v_pk_fma_f32 v[68:69], v[68:69], 0.5, v[72:73] op_sel_hi:[1,0,1]
	v_pk_fma_f32 v[66:67], v[66:67], 0.5, v[70:71] op_sel_hi:[1,0,1]
	global_store_dwordx4 v[100:101], v[66:69], off offset:576
.LBB0_3431:
	s_or_b64 exec, exec, s[8:9]
	s_addk_i32 s5, 0x4080
	s_movk_i32 s10, 0x4080
	v_or_b32_e32 v66, s5, v1
	s_ashr_i32 s5, s5, 13
	v_cmp_gt_i32_e32 vcc, s10, v66
	s_and_saveexec_b64 s[8:9], vcc
	s_cbranch_execz .LBB0_3433
	s_movk_i32 s11, 0x4000
	v_readlane_b32 s20, v228, 17
	v_add_u32_e32 v1, 0xffffc002, v66
	v_mov_b32_e32 v67, s5
	v_cmp_gt_i32_e32 vcc, s11, v66
	v_readlane_b32 s21, v228, 18
	s_mov_b32 s11, 0x9000
	v_cndmask_b32_e32 v1, v1, v67, vcc
	v_mov_b64_e32 v[68:69], s[20:21]
	v_mad_i64_i32 v[68:69], s[20:21], v1, s11, v[68:69]
	s_mov_b64 s[20:21], 0x2000
	v_ashrrev_i32_e32 v67, 31, v66
	v_lshl_add_u64 v[80:81], v[68:69], 0, s[20:21]
	v_lshlrev_b64 v[68:69], 12, v[66:67]
	v_add_u32_e32 v82, 0xffffc000, v66
	v_mov_b32_e32 v83, 0
	v_lshl_add_u64 v[76:77], s[6:7], 0, v[68:69]
	v_lshlrev_b64 v[68:69], 12, v[82:83]
	v_mov_b32_e32 v135, v83
	v_lshl_add_u64 v[68:69], s[14:15], 0, v[68:69]
	v_lshlrev_b64 v[78:79], 2, v[134:135]
	v_cndmask_b32_e32 v73, v69, v77, vcc
	v_cndmask_b32_e32 v72, v68, v76, vcc
	v_lshl_add_u64 v[68:69], v[80:81], 0, v[78:79]
	global_load_dwordx4 v[68:71], v[68:69], off
	v_lshl_add_u64 v[84:85], v[72:73], 0, v[78:79]
	global_load_dwordx4 v[72:75], v[84:85], off
	v_mov_b32_e32 v137, v83
	v_lshl_add_u64 v[86:87], v[76:77], 0, v[78:79]
	v_lshl_add_u64 v[76:77], v[136:137], 2, v[80:81]
	global_load_dwordx4 v[76:79], v[76:77], off
	v_or_b32_e32 v82, 0x80, v134
	s_waitcnt vmcnt(0) lgkmcnt(0)
	v_pk_mul_f32 v[64:65], v[64:65], v[70:71]
	v_pk_mul_f32 v[62:63], v[62:63], v[68:69]
	v_pk_fma_f32 v[64:65], v[64:65], 0.5, v[74:75] op_sel_hi:[1,0,1]
	v_pk_fma_f32 v[62:63], v[62:63], 0.5, v[72:73] op_sel_hi:[1,0,1]
	global_store_dwordx4 v[86:87], v[62:65], off
	global_load_dwordx4 v[62:65], v[84:85], off offset:64
	v_pk_mul_f32 v[60:61], v[60:61], v[78:79]
	v_pk_mul_f32 v[58:59], v[58:59], v[76:77]
	v_lshl_add_u64 v[68:69], v[82:83], 2, v[80:81]
	global_load_dwordx4 v[68:71], v[68:69], off
	v_or_b32_e32 v82, 0x90, v134
	s_waitcnt vmcnt(0) lgkmcnt(0)
	v_pk_fma_f32 v[60:61], v[60:61], 0.5, v[64:65] op_sel_hi:[1,0,1]
	v_pk_fma_f32 v[58:59], v[58:59], 0.5, v[62:63] op_sel_hi:[1,0,1]
	global_store_dwordx4 v[86:87], v[58:61], off offset:64
	global_load_dwordx4 v[58:61], v[84:85], off offset:512
	v_lshl_add_u64 v[62:63], v[82:83], 2, v[80:81]
	global_load_dwordx4 v[62:65], v[62:63], off
	v_pk_mul_f32 v[56:57], v[56:57], v[70:71]
	v_pk_mul_f32 v[54:55], v[54:55], v[68:69]
	s_waitcnt vmcnt(0) lgkmcnt(0)
	v_pk_fma_f32 v[56:57], v[56:57], 0.5, v[60:61] op_sel_hi:[1,0,1]
	v_pk_fma_f32 v[54:55], v[54:55], 0.5, v[58:59] op_sel_hi:[1,0,1]
	global_store_dwordx4 v[86:87], v[54:57], off offset:512
	global_load_dwordx4 v[54:57], v[84:85], off offset:576
	v_pk_mul_f32 v[52:53], v[52:53], v[64:65]
	v_pk_mul_f32 v[50:51], v[50:51], v[62:63]
	s_waitcnt vmcnt(0) lgkmcnt(0)
	v_pk_fma_f32 v[52:53], v[52:53], 0.5, v[56:57] op_sel_hi:[1,0,1]
	v_pk_fma_f32 v[50:51], v[50:51], 0.5, v[54:55] op_sel_hi:[1,0,1]
	global_store_dwordx4 v[86:87], v[50:53], off offset:576
.LBB0_3433:
	s_or_b64 exec, exec, s[8:9]
	s_nop 0
	v_or_b32_e32 v50, 16, v66
	v_cmp_gt_i32_e32 vcc, s10, v50
	s_and_saveexec_b64 s[8:9], vcc
	s_cbranch_execz .LBB0_3435
	s_movk_i32 s10, 0x4000
	v_readlane_b32 s20, v228, 17
	v_add_u32_e32 v1, 0xffffc012, v66
	v_mov_b32_e32 v51, s5
	v_cmp_gt_i32_e32 vcc, s10, v50
	v_readlane_b32 s21, v228, 18
	s_mov_b32 s10, 0x9000
	v_cndmask_b32_e32 v1, v1, v51, vcc
	v_mov_b64_e32 v[52:53], s[20:21]
	v_ashrrev_i32_e32 v51, 31, v50
	v_mad_i64_i32 v[52:53], s[10:11], v1, s10, v[52:53]
	v_lshlrev_b64 v[50:51], 12, v[50:51]
	v_add_u32_e32 v64, 0xffffc010, v66
	v_mov_b32_e32 v65, 0
	s_mov_b64 s[10:11], 0x2000
	v_lshl_add_u64 v[58:59], s[6:7], 0, v[50:51]
	v_lshlrev_b64 v[50:51], 12, v[64:65]
	v_mov_b32_e32 v135, v65
	v_lshl_add_u64 v[62:63], v[52:53], 0, s[10:11]
	v_lshl_add_u64 v[50:51], s[14:15], 0, v[50:51]
	v_lshlrev_b64 v[60:61], 2, v[134:135]
	v_cndmask_b32_e32 v55, v51, v59, vcc
	v_cndmask_b32_e32 v54, v50, v58, vcc
	v_lshl_add_u64 v[50:51], v[62:63], 0, v[60:61]
	global_load_dwordx4 v[50:53], v[50:51], off
	v_lshl_add_u64 v[68:69], v[54:55], 0, v[60:61]
	global_load_dwordx4 v[54:57], v[68:69], off
	v_mov_b32_e32 v137, v65
	v_lshl_add_u64 v[70:71], v[58:59], 0, v[60:61]
	v_lshl_add_u64 v[58:59], v[136:137], 2, v[62:63]
	global_load_dwordx4 v[58:61], v[58:59], off
	v_or_b32_e32 v64, 0x80, v134
	s_waitcnt vmcnt(0) lgkmcnt(0)
	v_pk_mul_f32 v[48:49], v[48:49], v[52:53]
	v_pk_mul_f32 v[46:47], v[46:47], v[50:51]
	v_pk_fma_f32 v[48:49], v[48:49], 0.5, v[56:57] op_sel_hi:[1,0,1]
	v_pk_fma_f32 v[46:47], v[46:47], 0.5, v[54:55] op_sel_hi:[1,0,1]
	global_store_dwordx4 v[70:71], v[46:49], off
	global_load_dwordx4 v[46:49], v[68:69], off offset:64
	v_pk_mul_f32 v[44:45], v[44:45], v[60:61]
	v_pk_mul_f32 v[42:43], v[42:43], v[58:59]
	v_lshl_add_u64 v[50:51], v[64:65], 2, v[62:63]
	global_load_dwordx4 v[50:53], v[50:51], off
	v_or_b32_e32 v64, 0x90, v134
	s_waitcnt vmcnt(0) lgkmcnt(0)
	v_pk_fma_f32 v[44:45], v[44:45], 0.5, v[48:49] op_sel_hi:[1,0,1]
	v_pk_fma_f32 v[42:43], v[42:43], 0.5, v[46:47] op_sel_hi:[1,0,1]
	global_store_dwordx4 v[70:71], v[42:45], off offset:64
	global_load_dwordx4 v[42:45], v[68:69], off offset:512
	v_lshl_add_u64 v[46:47], v[64:65], 2, v[62:63]
	global_load_dwordx4 v[46:49], v[46:47], off
	v_pk_mul_f32 v[40:41], v[40:41], v[52:53]
	v_pk_mul_f32 v[38:39], v[38:39], v[50:51]
	s_waitcnt vmcnt(0) lgkmcnt(0)
	v_pk_fma_f32 v[40:41], v[40:41], 0.5, v[44:45] op_sel_hi:[1,0,1]
	v_pk_fma_f32 v[38:39], v[38:39], 0.5, v[42:43] op_sel_hi:[1,0,1]
	global_store_dwordx4 v[70:71], v[38:41], off offset:512
	global_load_dwordx4 v[38:41], v[68:69], off offset:576
	v_pk_mul_f32 v[36:37], v[36:37], v[48:49]
	v_pk_mul_f32 v[34:35], v[34:35], v[46:47]
	s_waitcnt vmcnt(0) lgkmcnt(0)
	v_pk_fma_f32 v[36:37], v[36:37], 0.5, v[40:41] op_sel_hi:[1,0,1]
	v_pk_fma_f32 v[34:35], v[34:35], 0.5, v[38:39] op_sel_hi:[1,0,1]
	global_store_dwordx4 v[70:71], v[34:37], off offset:576
.LBB0_3435:
	s_or_b64 exec, exec, s[8:9]
	s_nop 0
	v_or_b32_e32 v34, 32, v66
	s_movk_i32 s10, 0x4080
	v_cmp_gt_i32_e32 vcc, s10, v34
	s_and_saveexec_b64 s[8:9], vcc
	s_cbranch_execz .LBB0_3437
	s_movk_i32 s11, 0x4000
	v_readlane_b32 s20, v228, 17
	v_add_u32_e32 v1, 0xffffc022, v66
	v_mov_b32_e32 v35, s5
	v_cmp_gt_i32_e32 vcc, s11, v34
	v_readlane_b32 s21, v228, 18
	s_mov_b32 s11, 0x9000
	v_cndmask_b32_e32 v1, v1, v35, vcc
	v_mov_b64_e32 v[36:37], s[20:21]
	v_ashrrev_i32_e32 v35, 31, v34
	v_mad_i64_i32 v[36:37], s[20:21], v1, s11, v[36:37]
	v_lshlrev_b64 v[34:35], 12, v[34:35]
	v_add_u32_e32 v48, 0xffffc020, v66
	v_mov_b32_e32 v49, 0
	s_mov_b64 s[20:21], 0x2000
	v_lshl_add_u64 v[42:43], s[6:7], 0, v[34:35]
	v_lshlrev_b64 v[34:35], 12, v[48:49]
	v_mov_b32_e32 v135, v49
	v_lshl_add_u64 v[46:47], v[36:37], 0, s[20:21]
	v_lshl_add_u64 v[34:35], s[14:15], 0, v[34:35]
	v_lshlrev_b64 v[44:45], 2, v[134:135]
	v_cndmask_b32_e32 v39, v35, v43, vcc
	v_cndmask_b32_e32 v38, v34, v42, vcc
	v_lshl_add_u64 v[34:35], v[46:47], 0, v[44:45]
	global_load_dwordx4 v[34:37], v[34:35], off
	v_lshl_add_u64 v[50:51], v[38:39], 0, v[44:45]
	global_load_dwordx4 v[38:41], v[50:51], off
	v_mov_b32_e32 v137, v49
	v_lshl_add_u64 v[52:53], v[42:43], 0, v[44:45]
	v_lshl_add_u64 v[42:43], v[136:137], 2, v[46:47]
	global_load_dwordx4 v[42:45], v[42:43], off
	v_or_b32_e32 v48, 0x80, v134
	s_waitcnt vmcnt(0) lgkmcnt(0)
	v_pk_mul_f32 v[32:33], v[32:33], v[36:37]
	v_pk_mul_f32 v[30:31], v[30:31], v[34:35]
	v_pk_fma_f32 v[32:33], v[32:33], 0.5, v[40:41] op_sel_hi:[1,0,1]
	v_pk_fma_f32 v[30:31], v[30:31], 0.5, v[38:39] op_sel_hi:[1,0,1]
	global_store_dwordx4 v[52:53], v[30:33], off
	global_load_dwordx4 v[30:33], v[50:51], off offset:64
	v_pk_mul_f32 v[28:29], v[28:29], v[44:45]
	v_pk_mul_f32 v[26:27], v[26:27], v[42:43]
	v_lshl_add_u64 v[34:35], v[48:49], 2, v[46:47]
	global_load_dwordx4 v[34:37], v[34:35], off
	v_or_b32_e32 v48, 0x90, v134
	s_waitcnt vmcnt(0) lgkmcnt(0)
	v_pk_fma_f32 v[28:29], v[28:29], 0.5, v[32:33] op_sel_hi:[1,0,1]
	v_pk_fma_f32 v[26:27], v[26:27], 0.5, v[30:31] op_sel_hi:[1,0,1]
	global_store_dwordx4 v[52:53], v[26:29], off offset:64
	global_load_dwordx4 v[26:29], v[50:51], off offset:512
	v_lshl_add_u64 v[30:31], v[48:49], 2, v[46:47]
	global_load_dwordx4 v[30:33], v[30:31], off
	v_pk_mul_f32 v[24:25], v[24:25], v[36:37]
	v_pk_mul_f32 v[22:23], v[22:23], v[34:35]
	s_waitcnt vmcnt(0) lgkmcnt(0)
	v_pk_fma_f32 v[24:25], v[24:25], 0.5, v[28:29] op_sel_hi:[1,0,1]
	v_pk_fma_f32 v[22:23], v[22:23], 0.5, v[26:27] op_sel_hi:[1,0,1]
	global_store_dwordx4 v[52:53], v[22:25], off offset:512
	global_load_dwordx4 v[22:25], v[50:51], off offset:576
	v_pk_mul_f32 v[20:21], v[20:21], v[32:33]
	v_pk_mul_f32 v[18:19], v[18:19], v[30:31]
	s_waitcnt vmcnt(0) lgkmcnt(0)
	v_pk_fma_f32 v[20:21], v[20:21], 0.5, v[24:25] op_sel_hi:[1,0,1]
	v_pk_fma_f32 v[18:19], v[18:19], 0.5, v[22:23] op_sel_hi:[1,0,1]
	global_store_dwordx4 v[52:53], v[18:21], off offset:576
.LBB0_3437:
	s_or_b64 exec, exec, s[8:9]
	s_nop 0
	v_or_b32_e32 v18, 48, v66
	v_cmp_gt_i32_e32 vcc, s10, v18
	s_and_saveexec_b64 s[8:9], vcc
	s_cbranch_execz .LBB0_3439
	s_movk_i32 s10, 0x4000
	v_cmp_gt_i32_e32 vcc, s10, v18
	v_readlane_b32 s10, v228, 17
	v_add_u32_e32 v1, 0xffffc032, v66
	v_mov_b32_e32 v19, s5
	v_readlane_b32 s11, v228, 18
	v_cndmask_b32_e32 v1, v1, v19, vcc
	s_mov_b32 s5, 0x9000
	v_mov_b64_e32 v[20:21], s[10:11]
	v_ashrrev_i32_e32 v19, 31, v18
	v_mad_i64_i32 v[20:21], s[10:11], v1, s5, v[20:21]
	v_lshlrev_b64 v[18:19], 12, v[18:19]
	v_add_u32_e32 v32, 0xffffc030, v66
	v_mov_b32_e32 v33, 0
	s_mov_b64 s[10:11], 0x2000
	v_lshl_add_u64 v[26:27], s[6:7], 0, v[18:19]
	v_lshlrev_b64 v[18:19], 12, v[32:33]
	v_mov_b32_e32 v135, v33
	v_lshl_add_u64 v[30:31], v[20:21], 0, s[10:11]
	v_lshl_add_u64 v[18:19], s[14:15], 0, v[18:19]
	v_lshlrev_b64 v[28:29], 2, v[134:135]
	v_cndmask_b32_e32 v23, v19, v27, vcc
	v_cndmask_b32_e32 v22, v18, v26, vcc
	v_lshl_add_u64 v[18:19], v[30:31], 0, v[28:29]
	global_load_dwordx4 v[18:21], v[18:19], off
	v_lshl_add_u64 v[34:35], v[22:23], 0, v[28:29]
	global_load_dwordx4 v[22:25], v[34:35], off
	v_mov_b32_e32 v137, v33
	v_lshl_add_u64 v[36:37], v[26:27], 0, v[28:29]
	v_lshl_add_u64 v[26:27], v[136:137], 2, v[30:31]
	global_load_dwordx4 v[26:29], v[26:27], off
	v_or_b32_e32 v32, 0x80, v134
	s_waitcnt vmcnt(0) lgkmcnt(0)
	v_pk_mul_f32 v[16:17], v[16:17], v[20:21]
	v_pk_mul_f32 v[14:15], v[14:15], v[18:19]
	v_pk_fma_f32 v[16:17], v[16:17], 0.5, v[24:25] op_sel_hi:[1,0,1]
	v_pk_fma_f32 v[14:15], v[14:15], 0.5, v[22:23] op_sel_hi:[1,0,1]
	global_store_dwordx4 v[36:37], v[14:17], off
	global_load_dwordx4 v[14:17], v[34:35], off offset:64
	v_pk_mul_f32 v[12:13], v[12:13], v[28:29]
	v_pk_mul_f32 v[10:11], v[10:11], v[26:27]
	v_lshl_add_u64 v[18:19], v[32:33], 2, v[30:31]
	global_load_dwordx4 v[18:21], v[18:19], off
	v_or_b32_e32 v32, 0x90, v134
	s_waitcnt vmcnt(0) lgkmcnt(0)
	v_pk_fma_f32 v[12:13], v[12:13], 0.5, v[16:17] op_sel_hi:[1,0,1]
	v_pk_fma_f32 v[10:11], v[10:11], 0.5, v[14:15] op_sel_hi:[1,0,1]
	global_store_dwordx4 v[36:37], v[10:13], off offset:64
	global_load_dwordx4 v[10:13], v[34:35], off offset:512
	v_lshl_add_u64 v[14:15], v[32:33], 2, v[30:31]
	global_load_dwordx4 v[14:17], v[14:15], off
	v_pk_mul_f32 v[8:9], v[8:9], v[20:21]
	v_pk_mul_f32 v[6:7], v[6:7], v[18:19]
	s_waitcnt vmcnt(0) lgkmcnt(0)
	v_pk_fma_f32 v[8:9], v[8:9], 0.5, v[12:13] op_sel_hi:[1,0,1]
	v_pk_fma_f32 v[6:7], v[6:7], 0.5, v[10:11] op_sel_hi:[1,0,1]
	global_store_dwordx4 v[36:37], v[6:9], off offset:512
	global_load_dwordx4 v[6:9], v[34:35], off offset:576
	v_pk_mul_f32 v[4:5], v[4:5], v[16:17]
	v_pk_mul_f32 v[2:3], v[2:3], v[14:15]
	s_waitcnt vmcnt(0) lgkmcnt(0)
	v_pk_fma_f32 v[4:5], v[4:5], 0.5, v[8:9] op_sel_hi:[1,0,1]
	v_pk_fma_f32 v[2:3], v[2:3], 0.5, v[6:7] op_sel_hi:[1,0,1]
	global_store_dwordx4 v[36:37], v[2:5], off offset:576

.LBB0_3447:
	s_or_b64 exec, exec, s[6:7]
	v_mov_b32_e32 v1, v0
	v_mov_b64_e32 v[2:3], s[0:1]
	s_barrier
	global_load_dwordx2 v[2:3], v[2:3], off offset:88 sc0 sc1
	s_waitcnt vmcnt(0)
	v_readfirstlane_b32 s5, v1
	s_ashr_i32 s5, s5, 6
	s_cmp_gt_i32 s5, 7
	v_and_b32_e32 v131, 63, v1
	s_cbranch_scc1 .LBB0_3450
	v_mov_b32_e32 v91, 0
	v_lshlrev_b32_e32 v90, 4, v131
	s_waitcnt lgkmcnt(0)
	v_lshl_add_u64 v[2:3], v[2:3], 0, v[90:91]
	s_movk_i32 s6, 0x4000
	v_add_co_u32_e32 v18, vcc, s6, v2
	s_lshl_b32 s6, s40, 5
	s_nop 0
	v_addc_co_u32_e32 v19, vcc, 0, v3, vcc
	global_load_dwordx4 v[2:5], v[18:19], off
	global_load_dwordx4 v[6:9], v[18:19], off offset:1024
	global_load_dwordx4 v[10:13], v[18:19], off offset:2048
	global_load_dwordx4 v[14:17], v[18:19], off offset:3072
	v_mbcnt_lo_u32_b32 v18, -1, 0
	v_mbcnt_hi_u32_b32 v18, -1, v18
	v_and_b32_e32 v19, 64, v18
	v_add_u32_e32 v19, 64, v19
	v_xor_b32_e32 v20, 1, v18
	v_cmp_lt_i32_e32 vcc, v20, v19
	s_lshl_b32 s7, s5, 2
	s_add_i32 s13, s6, 0x20a0
	v_cndmask_b32_e32 v20, v18, v20, vcc
	v_lshlrev_b32_e32 v133, 2, v20
	v_xor_b32_e32 v20, 2, v18
	v_cmp_lt_i32_e32 vcc, v20, v19
	s_add_i32 s6, s6, s7
	s_add_i32 s20, s6, 0x2080
	v_cndmask_b32_e32 v20, v18, v20, vcc
	v_lshlrev_b32_e32 v152, 2, v20
	v_xor_b32_e32 v20, 4, v18
	v_cmp_lt_i32_e32 vcc, v20, v19
	s_add_u32 s26, s38, 0x5803000
	s_addc_u32 s27, s39, 0
	v_cndmask_b32_e32 v20, v18, v20, vcc
	v_lshlrev_b32_e32 v153, 2, v20
	v_xor_b32_e32 v20, 8, v18
	v_cmp_lt_i32_e32 vcc, v20, v19
	s_ashr_i32 s21, s20, 31
	s_lshl_b64 s[6:7], s[20:21], 11
	v_cndmask_b32_e32 v20, v18, v20, vcc
	v_lshlrev_b32_e32 v154, 2, v20
	v_xor_b32_e32 v20, 16, v18
	v_cmp_lt_i32_e32 vcc, v20, v19
	v_lshl_or_b32 v92, v131, 3, s6
	v_mov_b32_e32 v93, s7
	v_cndmask_b32_e32 v20, v18, v20, vcc
	v_lshlrev_b32_e32 v155, 2, v20
	v_xor_b32_e32 v20, 32, v18
	v_cmp_lt_i32_e32 vcc, v20, v19
	s_lshl_b64 s[6:7], s[20:21], 12
	v_or_b32_e32 v94, s6, v90
	v_cndmask_b32_e32 v18, v18, v20, vcc
	v_lshlrev_b32_e32 v156, 2, v18
	v_lshlrev_b32_e32 v18, 2, v131
	v_or_b32_e32 v20, 0x100, v18
	v_or_b32_e32 v22, 0x200, v18
	v_or_b32_e32 v24, 0x300, v18
	v_mov_b32_e32 v95, s7
	v_mov_b32_e32 v157, 0x358637bd
	s_mov_b32 s21, 0xf800000
	v_mov_b32_e32 v158, 0x260
	v_lshlrev_b32_e32 v90, 2, v18
	s_movk_i32 s28, 0x7fff
	s_mov_b32 s29, 0xffff0000
	s_mov_b32 s30, 0xba00000
	v_lshlrev_b32_e32 v96, 2, v20
	v_mov_b32_e32 v97, v91
	v_lshlrev_b32_e32 v98, 2, v22
	v_mov_b32_e32 v99, v91
	v_lshlrev_b32_e32 v100, 2, v24
	v_mov_b32_e32 v101, v91
	s_mov_b32 s31, 0xba01000
	s_mov_b64 s[22:23], 0x10000
	s_mov_b64 s[24:25], 0x20000
.LBB0_3449:
	v_lshl_add_u64 v[18:19], s[38:39], 0, v[94:95]
	v_lshl_add_u64 v[22:23], s[38:39], 0, v[92:93]
	v_add_co_u32_e32 v20, vcc, 0x7800000, v18
	v_add_co_u32_e64 v102, s[6:7], s30, v22
	s_nop 0
	v_addc_co_u32_e32 v21, vcc, 0, v19, vcc
	v_addc_co_u32_e64 v103, s[6:7], 0, v23, s[6:7]
	v_add_co_u32_e64 v104, s[6:7], s31, v22
	v_add_co_u32_e32 v22, vcc, 0x7801000, v18
	s_nop 0
	v_addc_co_u32_e64 v105, s[6:7], 0, v23, s[6:7]
	global_load_dwordx4 v[78:81], v[20:21], off
	global_load_dwordx4 v[74:77], v[20:21], off offset:1024
	global_load_dwordx4 v[70:73], v[20:21], off offset:2048
	global_load_dwordx4 v[66:69], v[20:21], off offset:3072
	v_addc_co_u32_e32 v23, vcc, 0, v19, vcc
	v_add_co_u32_e32 v20, vcc, 0x7802000, v18
	global_load_dwordx4 v[62:65], v[22:23], off
	global_load_dwordx4 v[58:61], v[22:23], off offset:1024
	global_load_dwordx4 v[54:57], v[22:23], off offset:2048
	global_load_dwordx4 v[50:53], v[22:23], off offset:3072
	v_addc_co_u32_e32 v21, vcc, 0, v19, vcc
	global_load_dwordx4 v[46:49], v[20:21], off
	global_load_dwordx4 v[42:45], v[20:21], off offset:1024
	global_load_dwordx4 v[38:41], v[20:21], off offset:2048
	global_load_dwordx4 v[34:37], v[20:21], off offset:3072
	v_add_co_u32_e32 v18, vcc, 0x7803000, v18
	s_ashr_i32 s8, s20, 13
	s_nop 0
	v_addc_co_u32_e32 v19, vcc, 0, v19, vcc
	global_load_dwordx4 v[30:33], v[18:19], off
	global_load_dwordx4 v[26:29], v[18:19], off offset:1024
	global_load_dwordx4 v[22:25], v[18:19], off offset:2048
	s_nop 0
	global_load_dwordx4 v[18:21], v[18:19], off offset:3072
	s_add_i32 s9, s20, 0xffffc002
	s_cmpk_lt_i32 s20, 0x4000
	s_cselect_b32 s6, s8, s9
	s_addk_i32 s6, 0x82
	s_mul_hi_i32 s7, s6, 0x9000
	s_mul_i32 s6, s6, 0x9000
	s_add_u32 s6, s26, s6
	s_addc_u32 s7, s27, s7
	s_add_u32 s10, s6, 0x1000
	s_addc_u32 s11, s7, 0
	v_lshl_add_u64 v[122:123], s[6:7], 0, v[90:91]
	v_lshl_add_u64 v[86:87], s[10:11], 0, v[90:91]
	global_load_dwordx4 v[82:85], v[122:123], off
	s_add_i32 s6, s20, 0xffffc003
	global_load_dwordx4 v[86:89], v[86:87], off
	s_cmpk_lt_i32 s20, 0x3fff
	s_cselect_b32 s6, s8, s6
	s_addk_i32 s6, 0x82
	s_mul_hi_i32 s7, s6, 0x9000
	s_mul_i32 s6, s6, 0x9000
	s_add_u32 s6, s26, s6
	s_addc_u32 s7, s27, s7
	v_lshl_add_u64 v[138:139], s[10:11], 0, v[96:97]
	v_lshl_add_u64 v[134:135], s[10:11], 0, v[98:99]
	v_lshl_add_u64 v[128:129], s[10:11], 0, v[100:101]
	s_add_u32 s10, s6, 0x1000
	v_lshl_add_u64 v[110:111], s[6:7], 0, v[90:91]
	s_addc_u32 s11, s7, 0
	s_add_i32 s6, s20, 0xffffc004
	s_cmpk_lt_i32 s20, 0x3ffe
	s_cselect_b32 s6, s8, s6
	s_addk_i32 s6, 0x82
	s_mul_hi_i32 s7, s6, 0x9000
	s_mul_i32 s6, s6, 0x9000
	v_lshl_add_u64 v[124:125], s[10:11], 0, v[90:91]
	v_lshl_add_u64 v[118:119], s[10:11], 0, v[96:97]
	v_lshl_add_u64 v[114:115], s[10:11], 0, v[98:99]
	v_lshl_add_u64 v[112:113], s[10:11], 0, v[100:101]
	s_add_u32 s10, s26, s6
	s_addc_u32 s11, s27, s7
	s_add_u32 s6, s10, 0x1000
	s_addc_u32 s7, s11, 0
	s_add_i32 s9, s20, 0xffffc005
	s_cmpk_lt_i32 s20, 0x3ffd
	v_lshl_add_u64 v[142:143], s[6:7], 0, v[90:91]
	v_lshl_add_u64 v[140:141], s[6:7], 0, v[96:97]
	v_lshl_add_u64 v[136:137], s[6:7], 0, v[98:99]
	v_lshl_add_u64 v[126:127], s[6:7], 0, v[100:101]
	s_cselect_b32 s6, s8, s9
	s_addk_i32 s6, 0x82
	s_mul_hi_i32 s7, s6, 0x9000
	s_mul_i32 s6, s6, 0x9000
	s_add_u32 s6, s26, s6
	s_addc_u32 s7, s27, s7
	s_add_u32 s44, s6, 0x1000
	v_lshl_add_u64 v[106:107], s[6:7], 0, v[90:91]
	s_addc_u32 s45, s7, 0
	v_lshl_add_u64 v[108:109], s[10:11], 0, v[90:91]
	v_lshl_add_u64 v[120:121], s[44:45], 0, v[90:91]
	v_lshl_add_u64 v[116:117], s[44:45], 0, v[96:97]
	s_add_i32 s20, s20, 32
	v_lshl_add_u64 v[92:93], v[92:93], 0, s[22:23]
	s_waitcnt vmcnt(0) lgkmcnt(0)
	v_pk_mul_f32 v[144:145], v[80:81], v[80:81]
	v_pk_mul_f32 v[146:147], v[78:79], v[78:79]
	v_pk_mul_f32 v[148:149], v[76:77], v[76:77]
	v_pk_mul_f32 v[150:151], v[74:75], v[74:75]
	v_mul_f32_e32 v160, v71, v71
	v_mul_f32_e32 v162, v73, v73
	v_pk_mov_b32 v[164:165], v[146:147], v[144:145] op_sel:[1,0]
	v_mov_b32_e32 v147, v145
	v_pk_mov_b32 v[144:145], v[150:151], v[148:149] op_sel:[1,0]
	v_mov_b32_e32 v151, v149
	v_mul_f32_e32 v173, v68, v68
	v_mul_f32_e32 v175, v69, v69
	v_pk_fma_f32 v[148:149], v[70:71], v[70:71], v[160:161] op_sel_hi:[1,1,0]
	v_pk_fma_f32 v[160:161], v[72:73], v[72:73], v[162:163] op_sel_hi:[1,1,0]
	v_pk_mul_f32 v[162:163], v[64:65], v[64:65]
	v_pk_mul_f32 v[166:167], v[62:63], v[62:63]
	v_pk_mul_f32 v[168:169], v[60:61], v[60:61]
	v_pk_mul_f32 v[170:171], v[58:59], v[58:59]
	v_mul_f32_e32 v172, v55, v55
	v_mul_f32_e32 v174, v57, v57
	v_pk_add_f32 v[146:147], v[164:165], v[146:147]
	v_pk_add_f32 v[144:145], v[144:145], v[150:151]
	v_mul_f32_e32 v159, v66, v66
	v_mul_f32_e32 v183, v67, v67
	v_mov_b32_e32 v149, v173
	v_mov_b32_e32 v161, v175
	v_pk_mov_b32 v[150:151], v[166:167], v[162:163] op_sel:[1,0]
	v_mov_b32_e32 v167, v163
	v_pk_mov_b32 v[162:163], v[170:171], v[168:169] op_sel:[1,0]
	v_mov_b32_e32 v171, v169
	v_pk_fma_f32 v[164:165], v[54:55], v[54:55], v[172:173] op_sel_hi:[1,1,0]
	v_pk_fma_f32 v[168:169], v[56:57], v[56:57], v[174:175] op_sel_hi:[1,1,0]
	v_pk_mul_f32 v[172:173], v[48:49], v[48:49]
	v_pk_mul_f32 v[174:175], v[46:47], v[46:47]
	v_pk_add_f32 v[184:185], v[146:147], v[146:147] op_sel:[0,1] op_sel_hi:[1,0]
	v_pk_add_f32 v[186:187], v[144:145], v[144:145] op_sel:[0,1] op_sel_hi:[1,0]
	v_mul_f32_e32 v181, v52, v52
	v_pk_mul_f32 v[176:177], v[44:45], v[44:45]
	v_pk_mul_f32 v[178:179], v[42:43], v[42:43]
	v_mul_f32_e32 v180, v39, v39
	v_mul_f32_e32 v182, v41, v41
	v_pk_add_f32 v[160:161], v[148:149], v[160:161]
	v_pk_add_f32 v[144:145], v[150:151], v[166:167]
	v_pk_add_f32 v[146:147], v[162:163], v[170:171]
	v_pk_mov_b32 v[148:149], v[174:175], v[172:173] op_sel:[1,0]
	v_mov_b32_e32 v175, v173
	v_mov_b32_e32 v185, v159
	v_mov_b32_e32 v187, v183
	v_mul_f32_e32 v189, v50, v50
	v_mul_f32_e32 v194, v51, v51
	v_mul_f32_e32 v188, v53, v53
	v_mul_f32_e32 v197, v36, v36
	v_mul_f32_e32 v198, v37, v37
	v_pk_mov_b32 v[150:151], v[178:179], v[176:177] op_sel:[1,0]
	v_mov_b32_e32 v179, v177
	v_pk_fma_f32 v[162:163], v[38:39], v[38:39], v[180:181] op_sel_hi:[1,1,0]
	v_pk_fma_f32 v[166:167], v[40:41], v[40:41], v[182:183] op_sel_hi:[1,1,0]
	v_pk_add_f32 v[190:191], v[144:145], v[144:145] op_sel:[0,1] op_sel_hi:[1,0]
	v_pk_add_f32 v[192:193], v[146:147], v[146:147] op_sel:[0,1] op_sel_hi:[1,0]
	v_pk_add_f32 v[148:149], v[148:149], v[174:175]
	v_pk_add_f32 v[174:175], v[184:185], v[186:187]
	v_mov_b32_e32 v165, v181
	v_mov_b32_e32 v169, v188
	v_pk_mul_f32 v[170:171], v[32:33], v[32:33]
	v_pk_mul_f32 v[172:173], v[30:31], v[30:31]
	v_pk_mul_f32 v[176:177], v[28:29], v[28:29]
	v_pk_mul_f32 v[180:181], v[26:27], v[26:27]
	v_pk_add_f32 v[150:151], v[150:151], v[178:179]
	v_mov_b32_e32 v163, v197
	v_mov_b32_e32 v167, v198
	v_mov_b32_e32 v191, v189
	v_mov_b32_e32 v193, v194
	v_pk_add_f32 v[160:161], v[174:175], v[160:161]
	v_mul_f32_e32 v195, v34, v34
	v_mul_f32_e32 v196, v35, v35
	v_pk_add_f32 v[164:165], v[164:165], v[168:169]
	v_pk_mov_b32 v[168:169], v[172:173], v[170:171] op_sel:[1,0]
	v_mov_b32_e32 v173, v171
	v_pk_mov_b32 v[170:171], v[180:181], v[176:177] op_sel:[1,0]
	v_mov_b32_e32 v181, v177
	v_pk_add_f32 v[176:177], v[148:149], v[148:149] op_sel:[0,1] op_sel_hi:[1,0]
	v_pk_add_f32 v[178:179], v[150:151], v[150:151] op_sel:[0,1] op_sel_hi:[1,0]
	v_pk_add_f32 v[162:163], v[162:163], v[166:167]
	v_pk_add_f32 v[166:167], v[190:191], v[192:193]
	v_add_f32_e32 v159, v160, v161
	v_mov_b32_e32 v177, v195
	v_mov_b32_e32 v179, v196
	v_pk_add_f32 v[160:161], v[166:167], v[164:165]
	ds_bpermute_b32 v167, v133, v159
	v_pk_add_f32 v[164:165], v[176:177], v[178:179]
	v_add_f32_e32 v166, v160, v161
	v_pk_add_f32 v[160:161], v[164:165], v[162:163]
	ds_bpermute_b32 v162, v133, v166
	v_add_f32_e32 v160, v160, v161
	ds_bpermute_b32 v161, v133, v160
	s_waitcnt lgkmcnt(2)
	v_add_f32_e32 v159, v159, v167
	ds_bpermute_b32 v163, v152, v159
	s_waitcnt lgkmcnt(2)
	v_add_f32_e32 v162, v166, v162
	ds_bpermute_b32 v164, v152, v162
	s_waitcnt lgkmcnt(2)
	v_add_f32_e32 v160, v160, v161
	ds_bpermute_b32 v161, v152, v160
	s_waitcnt lgkmcnt(2)
	v_add_f32_e32 v159, v159, v163
	ds_bpermute_b32 v163, v153, v159
	s_waitcnt lgkmcnt(2)
	v_add_f32_e32 v162, v162, v164
	ds_bpermute_b32 v164, v153, v162
	s_waitcnt lgkmcnt(2)
	v_add_f32_e32 v160, v160, v161
	ds_bpermute_b32 v161, v153, v160
	s_waitcnt lgkmcnt(2)
	v_add_f32_e32 v159, v159, v163
	ds_bpermute_b32 v163, v154, v159
	s_waitcnt lgkmcnt(2)
	v_add_f32_e32 v162, v162, v164
	ds_bpermute_b32 v164, v154, v162
	s_waitcnt lgkmcnt(2)
	v_add_f32_e32 v160, v160, v161
	ds_bpermute_b32 v161, v154, v160
	s_waitcnt lgkmcnt(2)
	v_add_f32_e32 v159, v159, v163
	ds_bpermute_b32 v163, v155, v159
	s_waitcnt lgkmcnt(2)
	v_add_f32_e32 v162, v162, v164
	ds_bpermute_b32 v164, v155, v162
	s_waitcnt lgkmcnt(2)
	v_add_f32_e32 v160, v160, v161
	ds_bpermute_b32 v161, v155, v160
	s_waitcnt lgkmcnt(2)
	v_add_f32_e32 v159, v159, v163
	ds_bpermute_b32 v163, v156, v159
	s_waitcnt lgkmcnt(2)
	v_add_f32_e32 v162, v162, v164
	ds_bpermute_b32 v164, v156, v162
	s_waitcnt lgkmcnt(2)
	v_add_f32_e32 v160, v160, v161
	ds_bpermute_b32 v161, v156, v160
	s_waitcnt lgkmcnt(2)
	v_add_f32_e32 v159, v159, v163
	v_fmamk_f32 v159, v159, 0x3a800000, v157
	s_waitcnt lgkmcnt(1)
	v_add_f32_e32 v162, v162, v164
	v_mul_f32_e32 v163, 0x4f800000, v159
	v_cmp_gt_f32_e32 vcc, s21, v159
	v_fmamk_f32 v162, v162, 0x3a800000, v157
	s_waitcnt lgkmcnt(0)
	v_add_f32_e32 v160, v160, v161
	v_cndmask_b32_e32 v159, v159, v163, vcc
	v_mul_f32_e32 v161, 0x4f800000, v162
	v_cmp_gt_f32_e64 s[6:7], s21, v162
	v_sqrt_f32_e32 v163, v159
	v_fmamk_f32 v160, v160, 0x3a800000, v157
	v_cndmask_b32_e64 v161, v162, v161, s[6:7]
	v_mul_f32_e32 v162, 0x4f800000, v160
	v_cmp_gt_f32_e64 s[8:9], s21, v160
	v_sqrt_f32_e32 v164, v161
	v_add_u32_e32 v165, -1, v163
	v_cndmask_b32_e64 v160, v160, v162, s[8:9]
	v_sqrt_f32_e32 v162, v160
	v_add_u32_e32 v166, 1, v163
	v_fma_f32 v167, -v165, v163, v159
	v_pk_add_f32 v[148:149], v[168:169], v[172:173]
	v_fma_f32 v168, -v166, v163, v159
	v_add_u32_e32 v169, -1, v164
	v_cmp_ge_f32_e64 s[10:11], 0, v167
	v_pk_add_f32 v[150:151], v[170:171], v[180:181]
	v_add_u32_e32 v170, 1, v164
	v_cndmask_b32_e64 v163, v163, v165, s[10:11]
	v_fma_f32 v165, -v169, v164, v161
	v_cmp_lt_f32_e64 s[10:11], 0, v168
	v_fma_f32 v167, -v170, v164, v161
	v_add_u32_e32 v171, -1, v162
	v_cndmask_b32_e64 v163, v163, v166, s[10:11]
	v_cmp_ge_f32_e64 s[10:11], 0, v165
	v_add_u32_e32 v172, 1, v162
	v_fma_f32 v165, -v171, v162, v160
	v_cndmask_b32_e64 v164, v164, v169, s[10:11]
	v_cmp_lt_f32_e64 s[10:11], 0, v167
	v_fma_f32 v166, -v172, v162, v160
	v_mul_f32_e32 v167, 0x37800000, v163
	v_cndmask_b32_e64 v164, v164, v170, s[10:11]
	v_cmp_ge_f32_e64 s[10:11], 0, v165
	v_cndmask_b32_e32 v163, v163, v167, vcc
	v_cmp_class_f32_e32 vcc, v159, v158
	v_cndmask_b32_e64 v162, v162, v171, s[10:11]
	v_cmp_lt_f32_e64 s[10:11], 0, v166
	v_mul_f32_e32 v165, 0x37800000, v164
	v_cndmask_b32_e32 v159, v163, v159, vcc
	v_cndmask_b32_e64 v162, v162, v172, s[10:11]
	v_cndmask_b32_e64 v163, v164, v165, s[6:7]
	v_cmp_class_f32_e32 vcc, v161, v158
	v_mul_f32_e32 v164, 0x37800000, v162
	v_div_scale_f32 v165, s[6:7], v159, v159, 1.0
	v_cndmask_b32_e32 v161, v163, v161, vcc
	v_cndmask_b32_e64 v162, v162, v164, s[8:9]
	v_cmp_class_f32_e32 vcc, v160, v158
	v_rcp_f32_e32 v163, v165
	v_div_scale_f32 v164, s[8:9], v161, v161, 1.0
	v_cndmask_b32_e32 v162, v162, v160, vcc
	v_rcp_f32_e32 v168, v164
	v_div_scale_f32 v169, s[10:11], v162, v162, 1.0
	v_rcp_f32_e32 v171, v169
	v_fma_f32 v160, -v165, v163, 1.0
	v_div_scale_f32 v166, s[6:7], 1.0, v159, 1.0
	v_fmac_f32_e32 v163, v160, v163
	v_fma_f32 v160, -v164, v168, 1.0
	v_mul_f32_e32 v172, v166, v163
	v_div_scale_f32 v167, s[8:9], 1.0, v161, 1.0
	v_fmac_f32_e32 v168, v160, v168
	v_fma_f32 v160, -v169, v171, 1.0
	v_fma_f32 v173, -v165, v172, v166
	v_div_scale_f32 v170, s[10:11], 1.0, v162, 1.0
	v_mul_f32_e32 v174, v167, v168
	v_fmac_f32_e32 v171, v160, v171
	v_fmac_f32_e32 v172, v173, v163
	v_fma_f32 v160, -v164, v174, v167
	v_mul_f32_e32 v173, v170, v171
	v_fma_f32 v165, -v165, v172, v166
	s_mov_b64 vcc, s[6:7]
	v_fmac_f32_e32 v174, v160, v168
	v_fma_f32 v160, -v169, v173, v170
	v_div_fmas_f32 v163, v165, v163, v172
	v_fma_f32 v164, -v164, v174, v167
	v_fmac_f32_e32 v173, v160, v171
	v_div_fixup_f32 v160, v163, v159, 1.0
	s_mov_b64 vcc, s[8:9]
	v_div_fmas_f32 v159, v164, v168, v174
	v_fma_f32 v163, -v169, v173, v170
	v_pk_mul_f32 v[80:81], v[80:81], v[160:161] op_sel_hi:[1,0]
	v_pk_mul_f32 v[78:79], v[78:79], v[160:161] op_sel_hi:[1,0]
	s_mov_b64 vcc, s[10:11]
	v_pk_add_f32 v[88:89], v[88:89], 1.0 op_sel_hi:[1,0]
	v_pk_add_f32 v[86:87], v[86:87], 1.0 op_sel_hi:[1,0]
	v_pk_mul_f32 v[76:77], v[76:77], v[160:161] op_sel_hi:[1,0]
	v_pk_mul_f32 v[74:75], v[74:75], v[160:161] op_sel_hi:[1,0]
	v_pk_mul_f32 v[72:73], v[72:73], v[160:161] op_sel_hi:[1,0]
	v_pk_mul_f32 v[70:71], v[70:71], v[160:161] op_sel_hi:[1,0]
	v_pk_mul_f32 v[68:69], v[68:69], v[160:161] op_sel_hi:[1,0]
	v_pk_mul_f32 v[66:67], v[66:67], v[160:161] op_sel_hi:[1,0]
	v_div_fixup_f32 v160, v159, v161, 1.0
	v_div_fmas_f32 v159, v163, v171, v173
	v_pk_mul_f32 v[78:79], v[78:79], v[2:3]
	v_pk_mul_f32 v[80:81], v[80:81], v[4:5]
	v_pk_mul_f32 v[64:65], v[64:65], v[160:161] op_sel_hi:[1,0]
	v_pk_mul_f32 v[62:63], v[62:63], v[160:161] op_sel_hi:[1,0]
	v_pk_mul_f32 v[60:61], v[60:61], v[160:161] op_sel_hi:[1,0]
	v_pk_mul_f32 v[58:59], v[58:59], v[160:161] op_sel_hi:[1,0]
	v_pk_mul_f32 v[56:57], v[56:57], v[160:161] op_sel_hi:[1,0]
	v_pk_mul_f32 v[54:55], v[54:55], v[160:161] op_sel_hi:[1,0]
	v_pk_mul_f32 v[52:53], v[52:53], v[160:161] op_sel_hi:[1,0]
	v_pk_mul_f32 v[50:51], v[50:51], v[160:161] op_sel_hi:[1,0]
	v_div_fixup_f32 v160, v159, v162, 1.0
	v_pk_fma_f32 v[80:81], v[80:81], v[88:89], v[84:85]
	v_pk_fma_f32 v[78:79], v[78:79], v[86:87], v[82:83]
	v_pk_mul_f32 v[82:83], v[50:51], v[14:15]
	v_pk_mul_f32 v[84:85], v[52:53], v[16:17]
	v_pk_mul_f32 v[48:49], v[48:49], v[160:161] op_sel_hi:[1,0]
	v_pk_mul_f32 v[46:47], v[46:47], v[160:161] op_sel_hi:[1,0]
	v_bfe_u32 v50, v78, 16, 1
	v_bfe_u32 v52, v80, 16, 1
	v_bfe_u32 v51, v79, 16, 1
	v_bfe_u32 v53, v81, 16, 1
	v_pk_mul_f32 v[86:87], v[46:47], v[2:3]
	v_pk_mul_f32 v[88:89], v[48:49], v[4:5]
	v_add3_u32 v46, v78, v50, s28
	v_add3_u32 v48, v80, v52, s28
	v_add3_u32 v47, v79, v51, s28
	v_add3_u32 v49, v81, v53, s28
	v_lshrrev_b32_e32 v46, 16, v46
	v_lshrrev_b32_e32 v48, 16, v48
	v_and_or_b32 v46, v47, s29, v46
	v_and_or_b32 v47, v49, s29, v48
	global_store_dwordx2 v[102:103], v[46:47], off
	global_load_dwordx4 v[46:49], v[138:139], off
	s_nop 0
	global_load_dwordx4 v[50:53], v[122:123], off offset:1024
	v_pk_mul_f32 v[74:75], v[74:75], v[6:7]
	v_pk_mul_f32 v[76:77], v[76:77], v[8:9]
	v_pk_mul_f32 v[70:71], v[70:71], v[10:11]
	v_pk_mul_f32 v[72:73], v[72:73], v[12:13]
	v_pk_mul_f32 v[66:67], v[66:67], v[14:15]
	v_pk_mul_f32 v[68:69], v[68:69], v[16:17]
	v_pk_mul_f32 v[62:63], v[62:63], v[2:3]
	v_pk_mul_f32 v[64:65], v[64:65], v[4:5]
	v_pk_mul_f32 v[58:59], v[58:59], v[6:7]
	v_pk_mul_f32 v[60:61], v[60:61], v[8:9]
	v_pk_mul_f32 v[54:55], v[54:55], v[10:11]
	v_pk_mul_f32 v[56:57], v[56:57], v[12:13]
	v_pk_mul_f32 v[44:45], v[44:45], v[160:161] op_sel_hi:[1,0]
	v_pk_mul_f32 v[42:43], v[42:43], v[160:161] op_sel_hi:[1,0]
	v_pk_mul_f32 v[44:45], v[44:45], v[8:9]
	v_pk_mul_f32 v[42:43], v[42:43], v[6:7]
	v_pk_mul_f32 v[40:41], v[40:41], v[160:161] op_sel_hi:[1,0]
	v_pk_mul_f32 v[38:39], v[38:39], v[160:161] op_sel_hi:[1,0]
	v_pk_mul_f32 v[40:41], v[40:41], v[12:13]
	v_pk_mul_f32 v[38:39], v[38:39], v[10:11]
	v_pk_mul_f32 v[36:37], v[36:37], v[160:161] op_sel_hi:[1,0]
	v_pk_mul_f32 v[34:35], v[34:35], v[160:161] op_sel_hi:[1,0]
	v_pk_mul_f32 v[36:37], v[36:37], v[16:17]
	v_pk_mul_f32 v[34:35], v[34:35], v[14:15]
	v_mul_f32_e32 v182, v23, v23
	v_mul_f32_e32 v188, v25, v25
	v_mul_f32_e32 v199, v18, v18
	v_mul_f32_e32 v200, v19, v19
	v_mul_f32_e32 v201, v20, v20
	v_mul_f32_e32 v202, v21, v21
	v_pk_fma_f32 v[144:145], v[22:23], v[22:23], v[182:183] op_sel_hi:[1,1,0]
	v_pk_fma_f32 v[146:147], v[24:25], v[24:25], v[188:189] op_sel_hi:[1,1,0]
	v_mov_b32_e32 v145, v201
	v_mov_b32_e32 v147, v202
	v_lshl_add_u64 v[94:95], v[94:95], 0, s[24:25]
	s_cmp_lt_i32 s20, s13
	s_waitcnt vmcnt(0) lgkmcnt(0)
	v_pk_add_f32 v[48:49], v[48:49], 1.0 op_sel_hi:[1,0]
	v_pk_add_f32 v[46:47], v[46:47], 1.0 op_sel_hi:[1,0]
	v_pk_fma_f32 v[48:49], v[76:77], v[48:49], v[52:53]
	v_pk_fma_f32 v[46:47], v[74:75], v[46:47], v[50:51]
	v_bfe_u32 v52, v48, 16, 1
	v_bfe_u32 v50, v46, 16, 1
	v_bfe_u32 v51, v47, 16, 1
	v_bfe_u32 v53, v49, 16, 1
	v_add3_u32 v46, v46, v50, s28
	v_add3_u32 v48, v48, v52, s28
	v_add3_u32 v47, v47, v51, s28
	v_add3_u32 v49, v49, v53, s28
	v_lshrrev_b32_e32 v46, 16, v46
	v_lshrrev_b32_e32 v48, 16, v48
	v_and_or_b32 v46, v47, s29, v46
	v_and_or_b32 v47, v49, s29, v48
	global_store_dwordx2 v[102:103], v[46:47], off offset:512
	global_load_dwordx4 v[46:49], v[134:135], off
	s_nop 0
	global_load_dwordx4 v[50:53], v[122:123], off offset:2048
	s_waitcnt vmcnt(0) lgkmcnt(0)
	v_pk_add_f32 v[48:49], v[48:49], 1.0 op_sel_hi:[1,0]
	v_pk_add_f32 v[46:47], v[46:47], 1.0 op_sel_hi:[1,0]
	v_pk_fma_f32 v[48:49], v[72:73], v[48:49], v[52:53]
	v_pk_fma_f32 v[46:47], v[70:71], v[46:47], v[50:51]
	v_bfe_u32 v52, v48, 16, 1
	v_bfe_u32 v50, v46, 16, 1
	v_bfe_u32 v51, v47, 16, 1
	v_bfe_u32 v53, v49, 16, 1
	v_add3_u32 v46, v46, v50, s28
	v_add3_u32 v48, v48, v52, s28
	v_add3_u32 v47, v47, v51, s28
	v_add3_u32 v49, v49, v53, s28
	v_lshrrev_b32_e32 v46, 16, v46
	v_lshrrev_b32_e32 v48, 16, v48
	v_and_or_b32 v46, v47, s29, v46
	v_and_or_b32 v47, v49, s29, v48
	global_store_dwordx2 v[102:103], v[46:47], off offset:1024
	global_load_dwordx4 v[46:49], v[128:129], off
	s_nop 0
	global_load_dwordx4 v[50:53], v[122:123], off offset:3072
	s_waitcnt vmcnt(0) lgkmcnt(0)
	v_pk_add_f32 v[48:49], v[48:49], 1.0 op_sel_hi:[1,0]
	v_pk_add_f32 v[46:47], v[46:47], 1.0 op_sel_hi:[1,0]
	v_pk_fma_f32 v[48:49], v[68:69], v[48:49], v[52:53]
	v_pk_fma_f32 v[46:47], v[66:67], v[46:47], v[50:51]
	v_bfe_u32 v52, v48, 16, 1
	v_bfe_u32 v50, v46, 16, 1
	v_bfe_u32 v51, v47, 16, 1
	v_bfe_u32 v53, v49, 16, 1
	v_add3_u32 v46, v46, v50, s28
	v_add3_u32 v48, v48, v52, s28
	v_add3_u32 v47, v47, v51, s28
	v_add3_u32 v49, v49, v53, s28
	v_lshrrev_b32_e32 v46, 16, v46
	v_lshrrev_b32_e32 v48, 16, v48
	v_and_or_b32 v46, v47, s29, v46
	v_and_or_b32 v47, v49, s29, v48
	global_store_dwordx2 v[102:103], v[46:47], off offset:1536
	global_load_dwordx4 v[46:49], v[124:125], off
	s_nop 0
	global_load_dwordx4 v[50:53], v[110:111], off
	s_waitcnt vmcnt(0) lgkmcnt(0)
	v_pk_add_f32 v[48:49], v[48:49], 1.0 op_sel_hi:[1,0]
	v_pk_add_f32 v[46:47], v[46:47], 1.0 op_sel_hi:[1,0]
	v_pk_fma_f32 v[48:49], v[64:65], v[48:49], v[52:53]
	v_pk_fma_f32 v[46:47], v[62:63], v[46:47], v[50:51]
	v_bfe_u32 v52, v48, 16, 1
	v_bfe_u32 v50, v46, 16, 1
	v_bfe_u32 v51, v47, 16, 1
	v_bfe_u32 v53, v49, 16, 1
	v_add3_u32 v46, v46, v50, s28
	v_add3_u32 v48, v48, v52, s28
	v_add3_u32 v47, v47, v51, s28
	v_add3_u32 v49, v49, v53, s28
	v_lshrrev_b32_e32 v46, 16, v46
	v_lshrrev_b32_e32 v48, 16, v48
	v_and_or_b32 v46, v47, s29, v46
	v_and_or_b32 v47, v49, s29, v48
	global_store_dwordx2 v[102:103], v[46:47], off offset:2048
	global_load_dwordx4 v[46:49], v[118:119], off
	s_nop 0
	global_load_dwordx4 v[50:53], v[110:111], off offset:1024
	s_waitcnt vmcnt(0) lgkmcnt(0)
	v_pk_add_f32 v[48:49], v[48:49], 1.0 op_sel_hi:[1,0]
	v_pk_add_f32 v[46:47], v[46:47], 1.0 op_sel_hi:[1,0]
	v_pk_fma_f32 v[48:49], v[60:61], v[48:49], v[52:53]
	v_pk_fma_f32 v[46:47], v[58:59], v[46:47], v[50:51]
	v_bfe_u32 v52, v48, 16, 1
	v_bfe_u32 v50, v46, 16, 1
	v_bfe_u32 v51, v47, 16, 1
	v_bfe_u32 v53, v49, 16, 1
	v_add3_u32 v46, v46, v50, s28
	v_add3_u32 v48, v48, v52, s28
	v_add3_u32 v47, v47, v51, s28
	v_add3_u32 v49, v49, v53, s28
	v_lshrrev_b32_e32 v46, 16, v46
	v_lshrrev_b32_e32 v48, 16, v48
	v_and_or_b32 v46, v47, s29, v46
	v_and_or_b32 v47, v49, s29, v48
	global_store_dwordx2 v[102:103], v[46:47], off offset:2560
	global_load_dwordx4 v[46:49], v[114:115], off
	s_nop 0
	global_load_dwordx4 v[50:53], v[110:111], off offset:2048
	v_pk_add_f32 v[58:59], v[144:145], v[146:147]
	s_waitcnt vmcnt(0) lgkmcnt(0)
	v_pk_add_f32 v[48:49], v[48:49], 1.0 op_sel_hi:[1,0]
	v_pk_add_f32 v[46:47], v[46:47], 1.0 op_sel_hi:[1,0]
	v_pk_fma_f32 v[48:49], v[56:57], v[48:49], v[52:53]
	v_pk_fma_f32 v[46:47], v[54:55], v[46:47], v[50:51]
	v_bfe_u32 v52, v48, 16, 1
	v_bfe_u32 v50, v46, 16, 1
	v_bfe_u32 v51, v47, 16, 1
	v_bfe_u32 v53, v49, 16, 1
	v_add3_u32 v46, v46, v50, s28
	v_add3_u32 v48, v48, v52, s28
	v_add3_u32 v47, v47, v51, s28
	v_add3_u32 v49, v49, v53, s28
	v_lshrrev_b32_e32 v46, 16, v46
	v_lshrrev_b32_e32 v48, 16, v48
	v_and_or_b32 v46, v47, s29, v46
	v_and_or_b32 v47, v49, s29, v48
	global_store_dwordx2 v[102:103], v[46:47], off offset:3072
	global_load_dwordx4 v[46:49], v[112:113], off
	s_nop 0
	global_load_dwordx4 v[50:53], v[110:111], off offset:3072
	v_pk_add_f32 v[54:55], v[148:149], v[148:149] op_sel:[0,1] op_sel_hi:[1,0]
	v_pk_add_f32 v[56:57], v[150:151], v[150:151] op_sel:[0,1] op_sel_hi:[1,0]
	v_mov_b32_e32 v55, v199
	v_mov_b32_e32 v57, v200
	s_waitcnt vmcnt(0) lgkmcnt(0)
	v_pk_add_f32 v[48:49], v[48:49], 1.0 op_sel_hi:[1,0]
	v_pk_add_f32 v[46:47], v[46:47], 1.0 op_sel_hi:[1,0]
	v_pk_fma_f32 v[48:49], v[84:85], v[48:49], v[52:53]
	v_pk_fma_f32 v[46:47], v[82:83], v[46:47], v[50:51]
	v_bfe_u32 v52, v48, 16, 1
	v_bfe_u32 v50, v46, 16, 1
	v_bfe_u32 v51, v47, 16, 1
	v_bfe_u32 v53, v49, 16, 1
	v_add3_u32 v46, v46, v50, s28
	v_add3_u32 v48, v48, v52, s28
	v_add3_u32 v47, v47, v51, s28
	v_add3_u32 v49, v49, v53, s28
	v_lshrrev_b32_e32 v46, 16, v46
	v_lshrrev_b32_e32 v48, 16, v48
	v_and_or_b32 v46, v47, s29, v46
	v_and_or_b32 v47, v49, s29, v48
	global_store_dwordx2 v[102:103], v[46:47], off offset:3584
	global_load_dwordx4 v[46:49], v[142:143], off
	s_nop 0
	global_load_dwordx4 v[50:53], v[108:109], off
	s_waitcnt vmcnt(0) lgkmcnt(0)
	v_pk_add_f32 v[48:49], v[48:49], 1.0 op_sel_hi:[1,0]
	v_pk_add_f32 v[46:47], v[46:47], 1.0 op_sel_hi:[1,0]
	v_pk_fma_f32 v[48:49], v[88:89], v[48:49], v[52:53]
	v_pk_fma_f32 v[46:47], v[86:87], v[46:47], v[50:51]
	v_bfe_u32 v52, v48, 16, 1
	v_bfe_u32 v50, v46, 16, 1
	v_bfe_u32 v51, v47, 16, 1
	v_bfe_u32 v53, v49, 16, 1
	v_add3_u32 v46, v46, v50, s28
	v_add3_u32 v48, v48, v52, s28
	v_add3_u32 v47, v47, v51, s28
	v_add3_u32 v49, v49, v53, s28
	v_lshrrev_b32_e32 v46, 16, v46
	v_lshrrev_b32_e32 v48, 16, v48
	v_and_or_b32 v46, v47, s29, v46
	v_and_or_b32 v47, v49, s29, v48
	global_store_dwordx2 v[104:105], v[46:47], off
	global_load_dwordx4 v[46:49], v[140:141], off
	s_nop 0
	global_load_dwordx4 v[50:53], v[108:109], off offset:1024
	s_waitcnt vmcnt(0) lgkmcnt(0)
	v_pk_add_f32 v[48:49], v[48:49], 1.0 op_sel_hi:[1,0]
	v_pk_add_f32 v[46:47], v[46:47], 1.0 op_sel_hi:[1,0]
	v_pk_fma_f32 v[44:45], v[44:45], v[48:49], v[52:53]
	v_pk_fma_f32 v[42:43], v[42:43], v[46:47], v[50:51]
	v_bfe_u32 v48, v44, 16, 1
	v_bfe_u32 v46, v42, 16, 1
	v_bfe_u32 v47, v43, 16, 1
	v_bfe_u32 v49, v45, 16, 1
	v_add3_u32 v42, v42, v46, s28
	v_add3_u32 v44, v44, v48, s28
	v_add3_u32 v43, v43, v47, s28
	v_add3_u32 v45, v45, v49, s28
	v_lshrrev_b32_e32 v42, 16, v42
	v_lshrrev_b32_e32 v44, 16, v44
	v_and_or_b32 v42, v43, s29, v42
	v_and_or_b32 v43, v45, s29, v44
	global_store_dwordx2 v[104:105], v[42:43], off offset:512
	global_load_dwordx4 v[42:45], v[136:137], off
	s_nop 0
	global_load_dwordx4 v[46:49], v[108:109], off offset:2048
	v_pk_add_f32 v[50:51], v[54:55], v[56:57]
	s_waitcnt vmcnt(0) lgkmcnt(0)
	v_pk_add_f32 v[44:45], v[44:45], 1.0 op_sel_hi:[1,0]
	v_pk_add_f32 v[42:43], v[42:43], 1.0 op_sel_hi:[1,0]
	v_pk_fma_f32 v[40:41], v[40:41], v[44:45], v[48:49]
	v_pk_fma_f32 v[38:39], v[38:39], v[42:43], v[46:47]
	v_bfe_u32 v44, v40, 16, 1
	v_bfe_u32 v42, v38, 16, 1
	v_bfe_u32 v43, v39, 16, 1
	v_bfe_u32 v45, v41, 16, 1
	v_add3_u32 v38, v38, v42, s28
	v_add3_u32 v40, v40, v44, s28
	v_add3_u32 v39, v39, v43, s28
	v_add3_u32 v41, v41, v45, s28
	v_lshrrev_b32_e32 v38, 16, v38
	v_lshrrev_b32_e32 v40, 16, v40
	v_and_or_b32 v38, v39, s29, v38
	v_and_or_b32 v39, v41, s29, v40
	global_store_dwordx2 v[104:105], v[38:39], off offset:1024
	global_load_dwordx4 v[38:41], v[126:127], off
	s_nop 0
	global_load_dwordx4 v[42:45], v[108:109], off offset:3072
	v_pk_add_f32 v[50:51], v[50:51], v[58:59]
	s_waitcnt vmcnt(0) lgkmcnt(0)
	v_pk_add_f32 v[40:41], v[40:41], 1.0 op_sel_hi:[1,0]
	v_pk_add_f32 v[38:39], v[38:39], 1.0 op_sel_hi:[1,0]
	v_pk_fma_f32 v[36:37], v[36:37], v[40:41], v[44:45]
	v_pk_fma_f32 v[34:35], v[34:35], v[38:39], v[42:43]
	v_bfe_u32 v40, v36, 16, 1
	v_bfe_u32 v38, v34, 16, 1
	v_bfe_u32 v39, v35, 16, 1
	v_bfe_u32 v41, v37, 16, 1
	v_add3_u32 v34, v34, v38, s28
	v_add3_u32 v36, v36, v40, s28
	v_add3_u32 v35, v35, v39, s28
	v_add3_u32 v37, v37, v41, s28
	v_lshrrev_b32_e32 v34, 16, v34
	v_lshrrev_b32_e32 v36, 16, v36
	v_and_or_b32 v34, v35, s29, v34
	v_and_or_b32 v35, v37, s29, v36
	global_store_dwordx2 v[104:105], v[34:35], off offset:1536
	global_load_dwordx4 v[34:37], v[120:121], off
	s_nop 0
	global_load_dwordx4 v[38:41], v[106:107], off
	v_add_f32_e32 v50, v50, v51
	ds_bpermute_b32 v51, v133, v50
	s_waitcnt lgkmcnt(0)
	v_add_f32_e32 v50, v50, v51
	ds_bpermute_b32 v51, v152, v50
	s_waitcnt lgkmcnt(0)
	v_add_f32_e32 v50, v50, v51
	ds_bpermute_b32 v46, v153, v50
	s_waitcnt lgkmcnt(0)
	v_add_f32_e32 v46, v50, v46
	ds_bpermute_b32 v47, v154, v46
	s_waitcnt lgkmcnt(0)
	v_add_f32_e32 v46, v46, v47
	ds_bpermute_b32 v47, v155, v46
	s_waitcnt lgkmcnt(0)
	v_add_f32_e32 v46, v46, v47
	ds_bpermute_b32 v47, v156, v46
	s_waitcnt lgkmcnt(0)
	v_add_f32_e32 v46, v46, v47
	v_fmamk_f32 v46, v46, 0x3a800000, v157
	v_mul_f32_e32 v47, 0x4f800000, v46
	v_cmp_gt_f32_e32 vcc, s21, v46
	s_waitcnt vmcnt(0)
	v_pk_add_f32 v[36:37], v[36:37], 1.0 op_sel_hi:[1,0]
	v_cndmask_b32_e32 v42, v46, v47, vcc
	v_sqrt_f32_e32 v43, v42
	v_pk_add_f32 v[34:35], v[34:35], 1.0 op_sel_hi:[1,0]
	v_add_u32_e32 v44, -1, v43
	v_add_u32_e32 v45, 1, v43
	v_fma_f32 v46, -v44, v43, v42
	v_fma_f32 v47, -v45, v43, v42
	v_cmp_ge_f32_e64 s[6:7], 0, v46
	s_nop 1
	v_cndmask_b32_e64 v43, v43, v44, s[6:7]
	v_cmp_lt_f32_e64 s[6:7], 0, v47
	s_nop 1
	v_cndmask_b32_e64 v43, v43, v45, s[6:7]
	v_mul_f32_e32 v44, 0x37800000, v43
	v_cndmask_b32_e32 v43, v43, v44, vcc
	v_cmp_class_f32_e32 vcc, v42, v158
	s_nop 1
	v_cndmask_b32_e32 v42, v43, v42, vcc
	v_div_scale_f32 v43, s[6:7], v42, v42, 1.0
	v_rcp_f32_e32 v45, v43
	v_div_scale_f32 v44, vcc, 1.0, v42, 1.0
	v_fma_f32 v46, -v43, v45, 1.0
	v_fmac_f32_e32 v45, v46, v45
	v_mul_f32_e32 v46, v44, v45
	v_fma_f32 v47, -v43, v46, v44
	v_fmac_f32_e32 v46, v47, v45
	v_fma_f32 v43, -v43, v46, v44
	v_div_fmas_f32 v43, v43, v45, v46
	v_div_fixup_f32 v42, v43, v42, 1.0
	v_pk_mul_f32 v[32:33], v[32:33], v[42:43] op_sel_hi:[1,0]
	v_pk_mul_f32 v[30:31], v[30:31], v[42:43] op_sel_hi:[1,0]
	v_pk_mul_f32 v[32:33], v[32:33], v[4:5]
	v_pk_mul_f32 v[30:31], v[30:31], v[2:3]
	v_pk_fma_f32 v[32:33], v[32:33], v[36:37], v[40:41]
	v_pk_fma_f32 v[30:31], v[30:31], v[34:35], v[38:39]
	v_bfe_u32 v36, v32, 16, 1
	v_bfe_u32 v34, v30, 16, 1
	v_bfe_u32 v35, v31, 16, 1
	v_bfe_u32 v37, v33, 16, 1
	v_add3_u32 v30, v30, v34, s28
	v_add3_u32 v32, v32, v36, s28
	v_add3_u32 v31, v31, v35, s28
	v_add3_u32 v33, v33, v37, s28
	v_lshrrev_b32_e32 v30, 16, v30
	v_lshrrev_b32_e32 v32, 16, v32
	v_and_or_b32 v30, v31, s29, v30
	v_and_or_b32 v31, v33, s29, v32
	global_store_dwordx2 v[104:105], v[30:31], off offset:2048
	global_load_dwordx4 v[30:33], v[116:117], off
	s_nop 0
	global_load_dwordx4 v[34:37], v[106:107], off offset:1024
	v_pk_mul_f32 v[28:29], v[28:29], v[42:43] op_sel_hi:[1,0]
	v_pk_mul_f32 v[26:27], v[26:27], v[42:43] op_sel_hi:[1,0]
	v_pk_mul_f32 v[28:29], v[28:29], v[8:9]
	v_pk_mul_f32 v[26:27], v[26:27], v[6:7]
	v_lshl_add_u64 v[38:39], s[44:45], 0, v[98:99]
	v_pk_mul_f32 v[24:25], v[24:25], v[42:43] op_sel_hi:[1,0]
	v_pk_mul_f32 v[22:23], v[22:23], v[42:43] op_sel_hi:[1,0]
	v_pk_mul_f32 v[24:25], v[24:25], v[12:13]
	v_pk_mul_f32 v[22:23], v[22:23], v[10:11]
	v_pk_mul_f32 v[20:21], v[20:21], v[42:43] op_sel_hi:[1,0]
	v_pk_mul_f32 v[18:19], v[18:19], v[42:43] op_sel_hi:[1,0]
	v_pk_mul_f32 v[20:21], v[20:21], v[16:17]
	v_pk_mul_f32 v[18:19], v[18:19], v[14:15]
	s_waitcnt vmcnt(0) lgkmcnt(0)
	v_pk_add_f32 v[32:33], v[32:33], 1.0 op_sel_hi:[1,0]
	v_pk_add_f32 v[30:31], v[30:31], 1.0 op_sel_hi:[1,0]
	v_pk_fma_f32 v[28:29], v[28:29], v[32:33], v[36:37]
	v_pk_fma_f32 v[26:27], v[26:27], v[30:31], v[34:35]
	v_bfe_u32 v32, v28, 16, 1
	v_bfe_u32 v30, v26, 16, 1
	v_bfe_u32 v31, v27, 16, 1
	v_bfe_u32 v33, v29, 16, 1
	v_add3_u32 v26, v26, v30, s28
	v_add3_u32 v28, v28, v32, s28
	v_add3_u32 v27, v27, v31, s28
	v_add3_u32 v29, v29, v33, s28
	v_lshrrev_b32_e32 v26, 16, v26
	v_lshrrev_b32_e32 v28, 16, v28
	v_and_or_b32 v26, v27, s29, v26
	v_and_or_b32 v27, v29, s29, v28
	global_store_dwordx2 v[104:105], v[26:27], off offset:2560
	global_load_dwordx4 v[26:29], v[38:39], off
	s_nop 0
	global_load_dwordx4 v[30:33], v[106:107], off offset:2048
	v_lshl_add_u64 v[34:35], s[44:45], 0, v[100:101]
	s_waitcnt vmcnt(0) lgkmcnt(0)
	v_pk_add_f32 v[28:29], v[28:29], 1.0 op_sel_hi:[1,0]
	v_pk_add_f32 v[26:27], v[26:27], 1.0 op_sel_hi:[1,0]
	v_pk_fma_f32 v[24:25], v[24:25], v[28:29], v[32:33]
	v_pk_fma_f32 v[22:23], v[22:23], v[26:27], v[30:31]
	v_bfe_u32 v28, v24, 16, 1
	v_bfe_u32 v26, v22, 16, 1
	v_bfe_u32 v27, v23, 16, 1
	v_bfe_u32 v29, v25, 16, 1
	v_add3_u32 v22, v22, v26, s28
	v_add3_u32 v24, v24, v28, s28
	v_add3_u32 v23, v23, v27, s28
	v_add3_u32 v25, v25, v29, s28
	v_lshrrev_b32_e32 v22, 16, v22
	v_lshrrev_b32_e32 v24, 16, v24
	v_and_or_b32 v22, v23, s29, v22
	v_and_or_b32 v23, v25, s29, v24
	global_store_dwordx2 v[104:105], v[22:23], off offset:3072
	global_load_dwordx4 v[22:25], v[34:35], off
	s_nop 0
	global_load_dwordx4 v[26:29], v[106:107], off offset:3072
	s_waitcnt vmcnt(0) lgkmcnt(0)
	v_pk_add_f32 v[24:25], v[24:25], 1.0 op_sel_hi:[1,0]
	v_pk_add_f32 v[22:23], v[22:23], 1.0 op_sel_hi:[1,0]
	v_pk_fma_f32 v[20:21], v[20:21], v[24:25], v[28:29]
	v_pk_fma_f32 v[18:19], v[18:19], v[22:23], v[26:27]
	v_bfe_u32 v24, v20, 16, 1
	v_bfe_u32 v22, v18, 16, 1
	v_bfe_u32 v23, v19, 16, 1
	v_bfe_u32 v25, v21, 16, 1
	v_add3_u32 v18, v18, v22, s28
	v_add3_u32 v20, v20, v24, s28
	v_add3_u32 v19, v19, v23, s28
	v_add3_u32 v21, v21, v25, s28
	v_lshrrev_b32_e32 v18, 16, v18
	v_lshrrev_b32_e32 v20, 16, v20
	v_and_or_b32 v18, v19, s29, v18
	v_and_or_b32 v19, v21, s29, v20
	global_store_dwordx2 v[104:105], v[18:19], off offset:3584
	s_cbranch_scc1 .LBB0_3449

.LBB0_3470:
	v_mul_f32_e32 v150, 0xbfb8aa3b, v126
	v_exp_f32_e32 v151, v150
	v_lshl_add_u32 v150, s52, 8, v1
	v_lshl_or_b32 v152, s53, 7, v131
	v_mul_f32_e32 v158, 0xbfb8aa3b, v127
	v_add_f32_e32 v151, 1.0, v151
	v_div_scale_f32 v154, s[52:53], v151, v151, v126
	v_rcp_f32_e32 v155, v154
	v_div_scale_f32 v156, vcc, v126, v151, v126
	v_exp_f32_e32 v158, v158
	v_fma_f32 v157, -v154, v155, 1.0
	v_fmac_f32_e32 v155, v157, v155
	v_mul_f32_e32 v157, v156, v155
	v_fma_f32 v159, -v154, v157, v156
	v_fmac_f32_e32 v157, v159, v155
	v_fma_f32 v154, -v154, v157, v156
	v_add_f32_e32 v156, 1.0, v158
	v_div_scale_f32 v158, s[52:53], v156, v156, v127
	v_rcp_f32_e32 v159, v158
	v_div_fmas_f32 v154, v154, v155, v157
	v_div_fixup_f32 v126, v154, v151, v126
	v_mul_f32_e32 v122, v126, v122
	v_fma_f32 v126, -v158, v159, 1.0
	v_fmac_f32_e32 v159, v126, v159
	v_div_scale_f32 v126, vcc, v127, v156, v127
	v_mul_f32_e32 v151, v126, v159
	v_fma_f32 v154, -v158, v151, v126
	v_fmac_f32_e32 v151, v154, v159
	v_mul_f32_e32 v154, 0xbfb8aa3b, v128
	v_exp_f32_e32 v154, v154
	v_fma_f32 v126, -v158, v151, v126
	v_div_fmas_f32 v126, v126, v159, v151
	v_div_fixup_f32 v126, v126, v156, v127
	v_add_f32_e32 v151, 1.0, v154
	v_div_scale_f32 v154, s[52:53], v151, v151, v128
	v_rcp_f32_e32 v155, v154
	v_mul_f32_e32 v123, v126, v123
	v_mul_f32_e32 v127, 0xbfb8aa3b, v129
	v_cvt_pk_bf16_f32 v122, v122, v123
	v_fma_f32 v123, -v154, v155, 1.0
	v_exp_f32_e32 v127, v127
	v_fmac_f32_e32 v155, v123, v155
	v_div_scale_f32 v123, vcc, v128, v151, v128
	v_mul_f32_e32 v126, v123, v155
	v_fma_f32 v156, -v154, v126, v123
	v_fmac_f32_e32 v126, v156, v155
	v_add_f32_e32 v127, 1.0, v127
	v_fma_f32 v123, -v154, v126, v123
	v_div_scale_f32 v154, s[52:53], v127, v127, v129
	v_rcp_f32_e32 v156, v154
	v_div_fmas_f32 v123, v123, v155, v126
	v_div_fixup_f32 v123, v123, v151, v128
	v_mul_f32_e32 v123, v123, v124
	v_fma_f32 v124, -v154, v156, 1.0
	v_fmac_f32_e32 v156, v124, v156
	v_div_scale_f32 v124, vcc, v129, v127, v129
	v_mul_f32_e32 v126, v124, v156
	v_fma_f32 v128, -v154, v126, v124
	v_fmac_f32_e32 v126, v128, v156
	v_mul_f32_e32 v128, 0xbfb8aa3b, v118
	v_exp_f32_e32 v128, v128
	v_fma_f32 v124, -v154, v126, v124
	v_div_fmas_f32 v124, v124, v156, v126
	v_div_fixup_f32 v124, v124, v127, v129
	v_add_f32_e32 v126, 1.0, v128
	v_div_scale_f32 v128, s[52:53], v126, v126, v118
	v_rcp_f32_e32 v151, v128
	v_mul_f32_e32 v124, v124, v125
	v_mul_f32_e32 v127, 0xbfb8aa3b, v119
	v_cvt_pk_bf16_f32 v123, v123, v124
	v_fma_f32 v124, -v128, v151, 1.0
	v_exp_f32_e32 v127, v127
	v_fmac_f32_e32 v151, v124, v151
	v_div_scale_f32 v124, vcc, v118, v126, v118
	v_mul_f32_e32 v125, v124, v151
	v_fma_f32 v129, -v128, v125, v124
	v_fmac_f32_e32 v125, v129, v151
	v_add_f32_e32 v127, 1.0, v127
	v_fma_f32 v124, -v128, v125, v124
	v_div_scale_f32 v128, s[52:53], v127, v127, v119
	v_rcp_f32_e32 v129, v128
	v_div_fmas_f32 v124, v124, v151, v125
	v_div_fixup_f32 v118, v124, v126, v118
	v_mul_f32_e32 v114, v118, v114
	v_fma_f32 v118, -v128, v129, 1.0
	v_fmac_f32_e32 v129, v118, v129
	v_div_scale_f32 v118, vcc, v119, v127, v119
	v_mul_f32_e32 v124, v118, v129
	v_fma_f32 v125, -v128, v124, v118
	v_fmac_f32_e32 v124, v125, v129
	v_mul_f32_e32 v125, 0xbfb8aa3b, v120
	v_exp_f32_e32 v125, v125
	v_fma_f32 v118, -v128, v124, v118
	v_div_fmas_f32 v118, v118, v129, v124
	v_div_fixup_f32 v118, v118, v127, v119
	v_add_f32_e32 v125, 1.0, v125
	v_div_scale_f32 v126, s[52:53], v125, v125, v120
	v_rcp_f32_e32 v128, v126
	v_mul_f32_e32 v115, v118, v115
	v_mul_f32_e32 v118, 0xbfb8aa3b, v121
	v_exp_f32_e32 v118, v118
	v_cvt_pk_bf16_f32 v124, v114, v115
	v_fma_f32 v114, -v126, v128, 1.0
	v_fmac_f32_e32 v128, v114, v128
	v_div_scale_f32 v114, vcc, v120, v125, v120
	v_mul_f32_e32 v115, v114, v128
	v_fma_f32 v119, -v126, v115, v114
	v_add_f32_e32 v118, 1.0, v118
	v_fmac_f32_e32 v115, v119, v128
	v_div_scale_f32 v119, s[52:53], v118, v118, v121
	v_fma_f32 v114, -v126, v115, v114
	v_rcp_f32_e32 v126, v119
	v_div_fmas_f32 v114, v114, v128, v115
	v_div_fixup_f32 v114, v114, v125, v120
	v_mul_f32_e32 v114, v114, v116
	v_fma_f32 v115, -v119, v126, 1.0
	v_fmac_f32_e32 v126, v115, v126
	v_div_scale_f32 v115, vcc, v121, v118, v121
	v_mul_f32_e32 v116, v115, v126
	v_fma_f32 v120, -v119, v116, v115
	v_fmac_f32_e32 v116, v120, v126
	v_fma_f32 v115, -v119, v116, v115
	v_div_fmas_f32 v115, v115, v126, v116
	v_div_fixup_f32 v115, v115, v118, v121
	v_mul_f32_e32 v115, v115, v117
	v_cvt_pk_bf16_f32 v125, v114, v115
	v_mul_f32_e32 v114, 0xbfb8aa3b, v110
	v_exp_f32_e32 v116, v114
	v_ashrrev_i32_e32 v153, 31, v152
	v_mov_b64_e32 v[114:115], s[18:19]
	v_mad_i64_i32 v[118:119], s[52:53], v150, s63, v[114:115]
	v_add_f32_e32 v120, 1.0, v116
	v_div_scale_f32 v121, s[52:53], v120, v120, v110
	v_rcp_f32_e32 v126, v121
	v_lshlrev_b64 v[116:117], 1, v[152:153]
	v_lshl_add_u64 v[118:119], v[118:119], 0, v[116:117]
	global_store_dwordx4 v[118:119], v[122:125], off
	v_fma_f32 v118, -v121, v126, 1.0
	v_fmac_f32_e32 v126, v118, v126
	v_mul_f32_e32 v122, 0xbfb8aa3b, v111
	v_div_scale_f32 v118, vcc, v110, v120, v110
	v_exp_f32_e32 v122, v122
	v_mul_f32_e32 v119, v118, v126
	v_fma_f32 v123, -v121, v119, v118
	v_fmac_f32_e32 v119, v123, v126
	v_fma_f32 v118, -v121, v119, v118
	v_add_f32_e32 v121, 1.0, v122
	v_div_scale_f32 v122, s[52:53], v121, v121, v111
	v_rcp_f32_e32 v123, v122
	v_div_fmas_f32 v118, v118, v126, v119
	v_div_fixup_f32 v110, v118, v120, v110
	v_mul_f32_e32 v106, v110, v106
	v_fma_f32 v110, -v122, v123, 1.0
	v_fmac_f32_e32 v123, v110, v123
	v_div_scale_f32 v110, vcc, v111, v121, v111
	v_mul_f32_e32 v118, v110, v123
	v_fma_f32 v119, -v122, v118, v110
	v_fmac_f32_e32 v118, v119, v123
	v_mul_f32_e32 v119, 0xbfb8aa3b, v112
	v_exp_f32_e32 v119, v119
	v_fma_f32 v110, -v122, v118, v110
	v_div_fmas_f32 v110, v110, v123, v118
	v_div_fixup_f32 v110, v110, v121, v111
	v_add_f32_e32 v118, 1.0, v119
	v_div_scale_f32 v119, s[52:53], v118, v118, v112
	v_rcp_f32_e32 v120, v119
	v_mul_f32_e32 v107, v110, v107
	v_mul_f32_e32 v111, 0xbfb8aa3b, v113
	v_cvt_pk_bf16_f32 v106, v106, v107
	v_fma_f32 v107, -v119, v120, 1.0
	v_exp_f32_e32 v111, v111
	v_fmac_f32_e32 v120, v107, v120
	v_div_scale_f32 v107, vcc, v112, v118, v112
	v_mul_f32_e32 v110, v107, v120
	v_fma_f32 v121, -v119, v110, v107
	v_fmac_f32_e32 v110, v121, v120
	v_add_f32_e32 v111, 1.0, v111
	v_fma_f32 v107, -v119, v110, v107
	v_div_scale_f32 v119, s[52:53], v111, v111, v113
	v_rcp_f32_e32 v121, v119
	v_div_fmas_f32 v107, v107, v120, v110
	v_div_fixup_f32 v107, v107, v118, v112
	v_mul_f32_e32 v107, v107, v108
	v_fma_f32 v108, -v119, v121, 1.0
	v_fmac_f32_e32 v121, v108, v121
	v_div_scale_f32 v108, vcc, v113, v111, v113
	v_mul_f32_e32 v110, v108, v121
	v_fma_f32 v112, -v119, v110, v108
	v_fmac_f32_e32 v110, v112, v121
	v_mul_f32_e32 v112, 0xbfb8aa3b, v102
	v_exp_f32_e32 v112, v112
	v_fma_f32 v108, -v119, v110, v108
	v_div_fmas_f32 v108, v108, v121, v110
	v_div_fixup_f32 v108, v108, v111, v113
	v_add_f32_e32 v110, 1.0, v112
	v_div_scale_f32 v112, s[52:53], v110, v110, v102
	v_rcp_f32_e32 v118, v112
	v_mul_f32_e32 v108, v108, v109
	v_mul_f32_e32 v111, 0xbfb8aa3b, v103
	v_cvt_pk_bf16_f32 v107, v107, v108
	v_fma_f32 v108, -v112, v118, 1.0
	v_exp_f32_e32 v111, v111
	v_fmac_f32_e32 v118, v108, v118
	v_div_scale_f32 v108, vcc, v102, v110, v102
	v_mul_f32_e32 v109, v108, v118
	v_fma_f32 v113, -v112, v109, v108
	v_fmac_f32_e32 v109, v113, v118
	v_add_f32_e32 v111, 1.0, v111
	v_fma_f32 v108, -v112, v109, v108
	v_div_scale_f32 v112, s[52:53], v111, v111, v103
	v_rcp_f32_e32 v113, v112
	v_div_fmas_f32 v108, v108, v118, v109
	v_div_fixup_f32 v102, v108, v110, v102
	v_mul_f32_e32 v98, v102, v98
	v_fma_f32 v102, -v112, v113, 1.0
	v_fmac_f32_e32 v113, v102, v113
	v_div_scale_f32 v102, vcc, v103, v111, v103
	v_mul_f32_e32 v108, v102, v113
	v_fma_f32 v109, -v112, v108, v102
	v_fmac_f32_e32 v108, v109, v113
	v_mul_f32_e32 v109, 0xbfb8aa3b, v104
	v_exp_f32_e32 v109, v109
	v_fma_f32 v102, -v112, v108, v102
	v_div_fmas_f32 v102, v102, v113, v108
	v_div_fixup_f32 v102, v102, v111, v103
	v_add_f32_e32 v109, 1.0, v109
	v_div_scale_f32 v110, s[52:53], v109, v109, v104
	v_rcp_f32_e32 v112, v110
	v_mul_f32_e32 v99, v102, v99
	v_mul_f32_e32 v102, 0xbfb8aa3b, v105
	v_exp_f32_e32 v102, v102
	v_cvt_pk_bf16_f32 v108, v98, v99
	v_fma_f32 v98, -v110, v112, 1.0
	v_fmac_f32_e32 v112, v98, v112
	v_div_scale_f32 v98, vcc, v104, v109, v104
	v_mul_f32_e32 v99, v98, v112
	v_fma_f32 v103, -v110, v99, v98
	v_add_f32_e32 v102, 1.0, v102
	v_fmac_f32_e32 v99, v103, v112
	v_div_scale_f32 v103, s[52:53], v102, v102, v105
	v_fma_f32 v98, -v110, v99, v98
	v_rcp_f32_e32 v110, v103
	v_div_fmas_f32 v98, v98, v112, v99
	v_div_fixup_f32 v98, v98, v109, v104
	v_mul_f32_e32 v98, v98, v100
	v_fma_f32 v99, -v103, v110, 1.0
	v_fmac_f32_e32 v110, v99, v110
	v_div_scale_f32 v99, vcc, v105, v102, v105
	v_mul_f32_e32 v100, v99, v110
	v_fma_f32 v104, -v103, v100, v99
	v_fmac_f32_e32 v100, v104, v110
	v_fma_f32 v99, -v103, v100, v99
	v_div_fmas_f32 v99, v99, v110, v100
	v_mul_f32_e32 v100, 0xbfb8aa3b, v94
	v_exp_f32_e32 v100, v100
	v_div_fixup_f32 v99, v99, v102, v105
	v_mul_f32_e32 v99, v99, v101
	v_cvt_pk_bf16_f32 v109, v98, v99
	v_add_f32_e32 v100, 1.0, v100
	v_div_scale_f32 v101, s[52:53], v100, v100, v94
	v_rcp_f32_e32 v102, v101
	v_or_b32_e32 v98, 16, v150
	v_mad_i64_i32 v[98:99], s[52:53], v98, s63, v[114:115]
	v_lshl_add_u64 v[98:99], v[98:99], 0, v[116:117]
	global_store_dwordx4 v[98:99], v[106:109], off
	v_fma_f32 v98, -v101, v102, 1.0
	v_mul_f32_e32 v103, 0xbfb8aa3b, v95
	v_fmac_f32_e32 v102, v98, v102
	v_div_scale_f32 v98, vcc, v94, v100, v94
	v_exp_f32_e32 v103, v103
	v_mul_f32_e32 v99, v98, v102
	v_fma_f32 v104, -v101, v99, v98
	v_fmac_f32_e32 v99, v104, v102
	v_fma_f32 v98, -v101, v99, v98
	v_add_f32_e32 v101, 1.0, v103
	v_div_scale_f32 v103, s[52:53], v101, v101, v95
	v_rcp_f32_e32 v104, v103
	v_div_fmas_f32 v98, v98, v102, v99
	v_div_fixup_f32 v94, v98, v100, v94
	v_mul_f32_e32 v90, v94, v90
	v_fma_f32 v94, -v103, v104, 1.0
	v_fmac_f32_e32 v104, v94, v104
	v_div_scale_f32 v94, vcc, v95, v101, v95
	v_mul_f32_e32 v98, v94, v104
	v_fma_f32 v99, -v103, v98, v94
	v_fmac_f32_e32 v98, v99, v104
	v_mul_f32_e32 v99, 0xbfb8aa3b, v96
	v_exp_f32_e32 v99, v99
	v_fma_f32 v94, -v103, v98, v94
	v_div_fmas_f32 v94, v94, v104, v98
	v_div_fixup_f32 v94, v94, v101, v95
	v_add_f32_e32 v98, 1.0, v99
	v_div_scale_f32 v99, s[52:53], v98, v98, v96
	v_rcp_f32_e32 v100, v99
	v_mul_f32_e32 v91, v94, v91
	v_mul_f32_e32 v95, 0xbfb8aa3b, v97
	v_cvt_pk_bf16_f32 v90, v90, v91
	v_fma_f32 v91, -v99, v100, 1.0
	v_exp_f32_e32 v95, v95
	v_fmac_f32_e32 v100, v91, v100
	v_div_scale_f32 v91, vcc, v96, v98, v96
	v_mul_f32_e32 v94, v91, v100
	v_fma_f32 v101, -v99, v94, v91
	v_fmac_f32_e32 v94, v101, v100
	v_add_f32_e32 v95, 1.0, v95
	v_fma_f32 v91, -v99, v94, v91
	v_div_scale_f32 v99, s[52:53], v95, v95, v97
	v_rcp_f32_e32 v101, v99
	v_div_fmas_f32 v91, v91, v100, v94
	v_div_fixup_f32 v91, v91, v98, v96
	v_mul_f32_e32 v91, v91, v92
	v_fma_f32 v92, -v99, v101, 1.0
	v_fmac_f32_e32 v101, v92, v101
	v_div_scale_f32 v92, vcc, v97, v95, v97
	v_mul_f32_e32 v94, v92, v101
	v_fma_f32 v96, -v99, v94, v92
	v_fmac_f32_e32 v94, v96, v101
	v_mul_f32_e32 v96, 0xbfb8aa3b, v86
	v_exp_f32_e32 v96, v96
	v_fma_f32 v92, -v99, v94, v92
	v_div_fmas_f32 v92, v92, v101, v94
	v_div_fixup_f32 v92, v92, v95, v97
	v_add_f32_e32 v94, 1.0, v96
	v_div_scale_f32 v96, s[52:53], v94, v94, v86
	v_rcp_f32_e32 v98, v96
	v_mul_f32_e32 v92, v92, v93
	v_mul_f32_e32 v95, 0xbfb8aa3b, v87
	v_cvt_pk_bf16_f32 v91, v91, v92
	v_fma_f32 v92, -v96, v98, 1.0
	v_exp_f32_e32 v95, v95
	v_fmac_f32_e32 v98, v92, v98
	v_div_scale_f32 v92, vcc, v86, v94, v86
	v_mul_f32_e32 v93, v92, v98
	v_fma_f32 v97, -v96, v93, v92
	v_fmac_f32_e32 v93, v97, v98
	v_add_f32_e32 v95, 1.0, v95
	v_fma_f32 v92, -v96, v93, v92
	v_div_scale_f32 v96, s[52:53], v95, v95, v87
	v_rcp_f32_e32 v97, v96
	v_div_fmas_f32 v92, v92, v98, v93
	v_div_fixup_f32 v86, v92, v94, v86
	v_mul_f32_e32 v82, v86, v82
	v_fma_f32 v86, -v96, v97, 1.0
	v_fmac_f32_e32 v97, v86, v97
	v_div_scale_f32 v86, vcc, v87, v95, v87
	v_mul_f32_e32 v92, v86, v97
	v_fma_f32 v93, -v96, v92, v86
	v_fmac_f32_e32 v92, v93, v97
	v_mul_f32_e32 v93, 0xbfb8aa3b, v88
	v_exp_f32_e32 v93, v93
	v_fma_f32 v86, -v96, v92, v86
	v_div_fmas_f32 v86, v86, v97, v92
	v_div_fixup_f32 v86, v86, v95, v87
	v_add_f32_e32 v93, 1.0, v93
	v_div_scale_f32 v94, s[52:53], v93, v93, v88
	v_rcp_f32_e32 v96, v94
	v_mul_f32_e32 v83, v86, v83
	v_mul_f32_e32 v86, 0xbfb8aa3b, v89
	v_exp_f32_e32 v86, v86
	v_cvt_pk_bf16_f32 v92, v82, v83
	v_fma_f32 v82, -v94, v96, 1.0
	v_fmac_f32_e32 v96, v82, v96
	v_div_scale_f32 v82, vcc, v88, v93, v88
	v_mul_f32_e32 v83, v82, v96
	v_fma_f32 v87, -v94, v83, v82
	v_add_f32_e32 v86, 1.0, v86
	v_fmac_f32_e32 v83, v87, v96
	v_div_scale_f32 v87, s[52:53], v86, v86, v89
	v_fma_f32 v82, -v94, v83, v82
	v_rcp_f32_e32 v94, v87
	v_div_fmas_f32 v82, v82, v96, v83
	v_div_fixup_f32 v82, v82, v93, v88
	v_mul_f32_e32 v82, v82, v84
	v_fma_f32 v83, -v87, v94, 1.0
	v_fmac_f32_e32 v94, v83, v94
	v_div_scale_f32 v83, vcc, v89, v86, v89
	v_mul_f32_e32 v84, v83, v94
	v_fma_f32 v88, -v87, v84, v83
	v_fmac_f32_e32 v84, v88, v94
	v_fma_f32 v83, -v87, v84, v83
	v_div_fmas_f32 v83, v83, v94, v84
	v_mul_f32_e32 v84, 0xbfb8aa3b, v78
	v_exp_f32_e32 v84, v84
	v_div_fixup_f32 v83, v83, v86, v89
	v_mul_f32_e32 v83, v83, v85
	v_cvt_pk_bf16_f32 v93, v82, v83
	v_add_f32_e32 v84, 1.0, v84
	v_div_scale_f32 v85, s[52:53], v84, v84, v78
	v_rcp_f32_e32 v86, v85
	v_or_b32_e32 v82, 32, v150
	v_mad_i64_i32 v[82:83], s[52:53], v82, s63, v[114:115]
	v_lshl_add_u64 v[82:83], v[82:83], 0, v[116:117]
	global_store_dwordx4 v[82:83], v[90:93], off
	v_fma_f32 v82, -v85, v86, 1.0
	v_mul_f32_e32 v87, 0xbfb8aa3b, v79
	v_fmac_f32_e32 v86, v82, v86
	v_div_scale_f32 v82, vcc, v78, v84, v78
	v_exp_f32_e32 v87, v87
	v_mul_f32_e32 v83, v82, v86
	v_fma_f32 v88, -v85, v83, v82
	v_fmac_f32_e32 v83, v88, v86
	v_fma_f32 v82, -v85, v83, v82
	v_add_f32_e32 v85, 1.0, v87
	v_div_scale_f32 v87, s[52:53], v85, v85, v79
	v_rcp_f32_e32 v88, v87
	v_div_fmas_f32 v82, v82, v86, v83
	v_div_fixup_f32 v78, v82, v84, v78
	v_mul_f32_e32 v74, v78, v74
	v_fma_f32 v78, -v87, v88, 1.0
	v_fmac_f32_e32 v88, v78, v88
	v_div_scale_f32 v78, vcc, v79, v85, v79
	v_mul_f32_e32 v82, v78, v88
	v_fma_f32 v83, -v87, v82, v78
	v_fmac_f32_e32 v82, v83, v88
	v_mul_f32_e32 v83, 0xbfb8aa3b, v80
	v_exp_f32_e32 v83, v83
	v_fma_f32 v78, -v87, v82, v78
	v_div_fmas_f32 v78, v78, v88, v82
	v_div_fixup_f32 v78, v78, v85, v79
	v_add_f32_e32 v82, 1.0, v83
	v_div_scale_f32 v83, s[52:53], v82, v82, v80
	v_rcp_f32_e32 v84, v83
	v_mul_f32_e32 v75, v78, v75
	v_mul_f32_e32 v79, 0xbfb8aa3b, v81
	v_cvt_pk_bf16_f32 v74, v74, v75
	v_fma_f32 v75, -v83, v84, 1.0
	v_exp_f32_e32 v79, v79
	v_fmac_f32_e32 v84, v75, v84
	v_div_scale_f32 v75, vcc, v80, v82, v80
	v_mul_f32_e32 v78, v75, v84
	v_fma_f32 v85, -v83, v78, v75
	v_fmac_f32_e32 v78, v85, v84
	v_add_f32_e32 v79, 1.0, v79
	v_fma_f32 v75, -v83, v78, v75
	v_div_scale_f32 v83, s[52:53], v79, v79, v81
	v_rcp_f32_e32 v85, v83
	v_div_fmas_f32 v75, v75, v84, v78
	v_div_fixup_f32 v75, v75, v82, v80
	v_mul_f32_e32 v75, v75, v76
	v_fma_f32 v76, -v83, v85, 1.0
	v_fmac_f32_e32 v85, v76, v85
	v_div_scale_f32 v76, vcc, v81, v79, v81
	v_mul_f32_e32 v78, v76, v85
	v_fma_f32 v80, -v83, v78, v76
	v_fmac_f32_e32 v78, v80, v85
	v_mul_f32_e32 v80, 0xbfb8aa3b, v70
	v_exp_f32_e32 v80, v80
	v_fma_f32 v76, -v83, v78, v76
	v_div_fmas_f32 v76, v76, v85, v78
	v_div_fixup_f32 v76, v76, v79, v81
	v_add_f32_e32 v78, 1.0, v80
	v_div_scale_f32 v80, s[52:53], v78, v78, v70
	v_rcp_f32_e32 v82, v80
	v_mul_f32_e32 v76, v76, v77
	v_mul_f32_e32 v79, 0xbfb8aa3b, v71
	v_cvt_pk_bf16_f32 v75, v75, v76
	v_fma_f32 v76, -v80, v82, 1.0
	v_exp_f32_e32 v79, v79
	v_fmac_f32_e32 v82, v76, v82
	v_div_scale_f32 v76, vcc, v70, v78, v70
	v_mul_f32_e32 v77, v76, v82
	v_fma_f32 v81, -v80, v77, v76
	v_fmac_f32_e32 v77, v81, v82
	v_add_f32_e32 v79, 1.0, v79
	v_fma_f32 v76, -v80, v77, v76
	v_div_scale_f32 v80, s[52:53], v79, v79, v71
	v_rcp_f32_e32 v81, v80
	v_div_fmas_f32 v76, v76, v82, v77
	v_div_fixup_f32 v70, v76, v78, v70
	v_mul_f32_e32 v66, v70, v66
	v_fma_f32 v70, -v80, v81, 1.0
	v_fmac_f32_e32 v81, v70, v81
	v_div_scale_f32 v70, vcc, v71, v79, v71
	v_mul_f32_e32 v76, v70, v81
	v_fma_f32 v77, -v80, v76, v70
	v_fmac_f32_e32 v76, v77, v81
	v_mul_f32_e32 v77, 0xbfb8aa3b, v72
	v_exp_f32_e32 v77, v77
	v_fma_f32 v70, -v80, v76, v70
	v_div_fmas_f32 v70, v70, v81, v76
	v_div_fixup_f32 v70, v70, v79, v71
	v_add_f32_e32 v77, 1.0, v77
	v_div_scale_f32 v78, s[52:53], v77, v77, v72
	v_rcp_f32_e32 v80, v78
	v_mul_f32_e32 v67, v70, v67
	v_mul_f32_e32 v70, 0xbfb8aa3b, v73
	v_exp_f32_e32 v70, v70
	v_cvt_pk_bf16_f32 v76, v66, v67
	v_fma_f32 v66, -v78, v80, 1.0
	v_fmac_f32_e32 v80, v66, v80
	v_div_scale_f32 v66, vcc, v72, v77, v72
	v_mul_f32_e32 v67, v66, v80
	v_fma_f32 v71, -v78, v67, v66
	v_add_f32_e32 v70, 1.0, v70
	v_fmac_f32_e32 v67, v71, v80
	v_div_scale_f32 v71, s[52:53], v70, v70, v73
	v_fma_f32 v66, -v78, v67, v66
	v_rcp_f32_e32 v78, v71
	v_div_fmas_f32 v66, v66, v80, v67
	v_div_fixup_f32 v66, v66, v77, v72
	v_mul_f32_e32 v66, v66, v68
	v_fma_f32 v67, -v71, v78, 1.0
	v_fmac_f32_e32 v78, v67, v78
	v_div_scale_f32 v67, vcc, v73, v70, v73
	v_mul_f32_e32 v68, v67, v78
	v_fma_f32 v72, -v71, v68, v67
	v_fmac_f32_e32 v68, v72, v78
	v_fma_f32 v67, -v71, v68, v67
	v_div_fmas_f32 v67, v67, v78, v68
	v_div_fixup_f32 v67, v67, v70, v73
	v_mul_f32_e32 v67, v67, v69
	v_cvt_pk_bf16_f32 v77, v66, v67
	v_mul_f32_e32 v66, 0xbfb8aa3b, v62
	v_exp_f32_e32 v68, v66
	v_or_b32_e32 v66, 48, v150
	v_mad_i64_i32 v[66:67], s[52:53], v66, s63, v[114:115]
	v_add_f32_e32 v68, 1.0, v68
	v_div_scale_f32 v69, s[52:53], v68, v68, v62
	v_rcp_f32_e32 v70, v69
	v_lshl_add_u64 v[66:67], v[66:67], 0, v[116:117]
	global_store_dwordx4 v[66:67], v[74:77], off
	v_mul_f32_e32 v72, 0xbfb8aa3b, v63
	v_fma_f32 v67, -v69, v70, 1.0
	v_fmac_f32_e32 v70, v67, v70
	v_div_scale_f32 v67, vcc, v62, v68, v62
	v_exp_f32_e32 v72, v72
	v_mul_f32_e32 v71, v67, v70
	v_fma_f32 v73, -v69, v71, v67
	v_fmac_f32_e32 v71, v73, v70
	v_fma_f32 v67, -v69, v71, v67
	v_add_f32_e32 v69, 1.0, v72
	v_div_scale_f32 v72, s[52:53], v69, v69, v63
	v_rcp_f32_e32 v73, v72
	v_div_fmas_f32 v67, v67, v70, v71
	v_div_fixup_f32 v62, v67, v68, v62
	v_mul_f32_e32 v58, v62, v58
	v_fma_f32 v62, -v72, v73, 1.0
	v_fmac_f32_e32 v73, v62, v73
	v_div_scale_f32 v62, vcc, v63, v69, v63
	v_mul_f32_e32 v67, v62, v73
	v_fma_f32 v68, -v72, v67, v62
	v_fmac_f32_e32 v67, v68, v73
	v_mul_f32_e32 v68, 0xbfb8aa3b, v64
	v_exp_f32_e32 v68, v68
	v_fma_f32 v62, -v72, v67, v62
	v_div_fmas_f32 v62, v62, v73, v67
	v_div_fixup_f32 v62, v62, v69, v63
	v_add_f32_e32 v67, 1.0, v68
	v_div_scale_f32 v68, s[52:53], v67, v67, v64
	v_rcp_f32_e32 v70, v68
	v_mul_f32_e32 v59, v62, v59
	v_mul_f32_e32 v63, 0xbfb8aa3b, v65
	v_cvt_pk_bf16_f32 v58, v58, v59
	v_fma_f32 v59, -v68, v70, 1.0
	v_exp_f32_e32 v63, v63
	v_fmac_f32_e32 v70, v59, v70
	v_div_scale_f32 v59, vcc, v64, v67, v64
	v_mul_f32_e32 v62, v59, v70
	v_fma_f32 v69, -v68, v62, v59
	v_fmac_f32_e32 v62, v69, v70
	v_add_f32_e32 v63, 1.0, v63
	v_fma_f32 v59, -v68, v62, v59
	v_div_scale_f32 v68, s[52:53], v63, v63, v65
	v_rcp_f32_e32 v69, v68
	v_div_fmas_f32 v59, v59, v70, v62
	v_div_fixup_f32 v59, v59, v67, v64
	v_mul_f32_e32 v59, v59, v60
	v_fma_f32 v60, -v68, v69, 1.0
	v_fmac_f32_e32 v69, v60, v69
	v_div_scale_f32 v60, vcc, v65, v63, v65
	v_mul_f32_e32 v62, v60, v69
	v_fma_f32 v64, -v68, v62, v60
	v_fmac_f32_e32 v62, v64, v69
	v_mul_f32_e32 v64, 0xbfb8aa3b, v54
	v_exp_f32_e32 v64, v64
	v_fma_f32 v60, -v68, v62, v60
	v_div_fmas_f32 v60, v60, v69, v62
	v_div_fixup_f32 v60, v60, v63, v65
	v_add_f32_e32 v62, 1.0, v64
	v_div_scale_f32 v64, s[52:53], v62, v62, v54
	v_rcp_f32_e32 v67, v64
	v_mul_f32_e32 v60, v60, v61
	v_mul_f32_e32 v63, 0xbfb8aa3b, v55
	v_cvt_pk_bf16_f32 v59, v59, v60
	v_fma_f32 v60, -v64, v67, 1.0
	v_exp_f32_e32 v63, v63
	v_fmac_f32_e32 v67, v60, v67
	v_div_scale_f32 v60, vcc, v54, v62, v54
	v_mul_f32_e32 v61, v60, v67
	v_fma_f32 v65, -v64, v61, v60
	v_fmac_f32_e32 v61, v65, v67
	v_add_f32_e32 v63, 1.0, v63
	v_fma_f32 v60, -v64, v61, v60
	v_div_scale_f32 v64, s[52:53], v63, v63, v55
	v_rcp_f32_e32 v65, v64
	v_div_fmas_f32 v60, v60, v67, v61
	v_div_fixup_f32 v54, v60, v62, v54
	v_mul_f32_e32 v50, v54, v50
	v_fma_f32 v54, -v64, v65, 1.0
	v_fmac_f32_e32 v65, v54, v65
	v_div_scale_f32 v54, vcc, v55, v63, v55
	v_mul_f32_e32 v60, v54, v65
	v_fma_f32 v61, -v64, v60, v54
	v_fmac_f32_e32 v60, v61, v65
	v_mul_f32_e32 v61, 0xbfb8aa3b, v56
	v_exp_f32_e32 v61, v61
	v_fma_f32 v54, -v64, v60, v54
	v_div_fmas_f32 v54, v54, v65, v60
	v_div_fixup_f32 v54, v54, v63, v55
	v_add_f32_e32 v61, 1.0, v61
	v_div_scale_f32 v62, s[52:53], v61, v61, v56
	v_rcp_f32_e32 v64, v62
	v_mul_f32_e32 v51, v54, v51
	v_mul_f32_e32 v54, 0xbfb8aa3b, v57
	v_exp_f32_e32 v54, v54
	v_cvt_pk_bf16_f32 v60, v50, v51
	v_fma_f32 v50, -v62, v64, 1.0
	v_fmac_f32_e32 v64, v50, v64
	v_div_scale_f32 v50, vcc, v56, v61, v56
	v_mul_f32_e32 v51, v50, v64
	v_fma_f32 v55, -v62, v51, v50
	v_add_f32_e32 v54, 1.0, v54
	v_fmac_f32_e32 v51, v55, v64
	v_div_scale_f32 v55, s[52:53], v54, v54, v57
	v_fma_f32 v50, -v62, v51, v50
	v_rcp_f32_e32 v62, v55
	v_div_fmas_f32 v50, v50, v64, v51
	v_div_fixup_f32 v50, v50, v61, v56
	v_mul_f32_e32 v50, v50, v52
	v_fma_f32 v51, -v55, v62, 1.0
	v_fmac_f32_e32 v62, v51, v62
	v_div_scale_f32 v51, vcc, v57, v54, v57
	v_mul_f32_e32 v52, v51, v62
	v_fma_f32 v56, -v55, v52, v51
	v_fmac_f32_e32 v52, v56, v62
	v_fma_f32 v51, -v55, v52, v51
	v_div_fmas_f32 v51, v51, v62, v52
	v_mul_f32_e32 v52, 0xbfb8aa3b, v46
	v_exp_f32_e32 v52, v52
	v_div_fixup_f32 v51, v51, v54, v57
	v_mul_f32_e32 v51, v51, v53
	v_add_u32_e32 v66, 0x80, v150
	v_add_f32_e32 v52, 1.0, v52
	v_div_scale_f32 v53, s[52:53], v52, v52, v46
	v_rcp_f32_e32 v54, v53
	v_cvt_pk_bf16_f32 v61, v50, v51
	v_mad_i64_i32 v[50:51], s[52:53], v66, s63, v[114:115]
	v_lshl_add_u64 v[50:51], v[50:51], 0, v[116:117]
	global_store_dwordx4 v[50:51], v[58:61], off
	v_fma_f32 v50, -v53, v54, 1.0
	v_mul_f32_e32 v55, 0xbfb8aa3b, v47
	v_fmac_f32_e32 v54, v50, v54
	v_div_scale_f32 v50, vcc, v46, v52, v46
	v_exp_f32_e32 v55, v55
	v_mul_f32_e32 v51, v50, v54
	v_fma_f32 v56, -v53, v51, v50
	v_fmac_f32_e32 v51, v56, v54
	v_fma_f32 v50, -v53, v51, v50
	v_add_f32_e32 v53, 1.0, v55
	v_div_scale_f32 v55, s[52:53], v53, v53, v47
	v_rcp_f32_e32 v56, v55
	v_div_fmas_f32 v50, v50, v54, v51
	v_div_fixup_f32 v46, v50, v52, v46
	v_mul_f32_e32 v42, v46, v42
	v_fma_f32 v46, -v55, v56, 1.0
	v_fmac_f32_e32 v56, v46, v56
	v_div_scale_f32 v46, vcc, v47, v53, v47
	v_mul_f32_e32 v50, v46, v56
	v_fma_f32 v51, -v55, v50, v46
	v_fmac_f32_e32 v50, v51, v56
	v_mul_f32_e32 v51, 0xbfb8aa3b, v48
	v_exp_f32_e32 v51, v51
	v_fma_f32 v46, -v55, v50, v46
	v_div_fmas_f32 v46, v46, v56, v50
	v_div_fixup_f32 v46, v46, v53, v47
	v_add_f32_e32 v50, 1.0, v51
	v_div_scale_f32 v51, s[52:53], v50, v50, v48
	v_rcp_f32_e32 v52, v51
	v_mul_f32_e32 v43, v46, v43
	v_mul_f32_e32 v47, 0xbfb8aa3b, v49
	v_cvt_pk_bf16_f32 v42, v42, v43
	v_fma_f32 v43, -v51, v52, 1.0
	v_exp_f32_e32 v47, v47
	v_fmac_f32_e32 v52, v43, v52
	v_div_scale_f32 v43, vcc, v48, v50, v48
	v_mul_f32_e32 v46, v43, v52
	v_fma_f32 v53, -v51, v46, v43
	v_fmac_f32_e32 v46, v53, v52
	v_add_f32_e32 v47, 1.0, v47
	v_fma_f32 v43, -v51, v46, v43
	v_div_scale_f32 v51, s[52:53], v47, v47, v49
	v_rcp_f32_e32 v53, v51
	v_div_fmas_f32 v43, v43, v52, v46
	v_div_fixup_f32 v43, v43, v50, v48
	v_mul_f32_e32 v43, v43, v44
	v_fma_f32 v44, -v51, v53, 1.0
	v_fmac_f32_e32 v53, v44, v53
	v_div_scale_f32 v44, vcc, v49, v47, v49
	v_mul_f32_e32 v46, v44, v53
	v_fma_f32 v48, -v51, v46, v44
	v_fmac_f32_e32 v46, v48, v53
	v_mul_f32_e32 v48, 0xbfb8aa3b, v38
	v_exp_f32_e32 v48, v48
	v_fma_f32 v44, -v51, v46, v44
	v_div_fmas_f32 v44, v44, v53, v46
	v_div_fixup_f32 v44, v44, v47, v49
	v_add_f32_e32 v46, 1.0, v48
	v_div_scale_f32 v48, s[52:53], v46, v46, v38
	v_rcp_f32_e32 v50, v48
	v_mul_f32_e32 v44, v44, v45
	v_mul_f32_e32 v47, 0xbfb8aa3b, v39
	v_cvt_pk_bf16_f32 v43, v43, v44
	v_fma_f32 v44, -v48, v50, 1.0
	v_exp_f32_e32 v47, v47
	v_fmac_f32_e32 v50, v44, v50
	v_div_scale_f32 v44, vcc, v38, v46, v38
	v_mul_f32_e32 v45, v44, v50
	v_fma_f32 v49, -v48, v45, v44
	v_fmac_f32_e32 v45, v49, v50
	v_add_f32_e32 v47, 1.0, v47
	v_fma_f32 v44, -v48, v45, v44
	v_div_scale_f32 v48, s[52:53], v47, v47, v39
	v_rcp_f32_e32 v49, v48
	v_div_fmas_f32 v44, v44, v50, v45
	v_div_fixup_f32 v38, v44, v46, v38
	v_mul_f32_e32 v34, v38, v34
	v_fma_f32 v38, -v48, v49, 1.0
	v_fmac_f32_e32 v49, v38, v49
	v_div_scale_f32 v38, vcc, v39, v47, v39
	v_mul_f32_e32 v44, v38, v49
	v_fma_f32 v45, -v48, v44, v38
	v_fmac_f32_e32 v44, v45, v49
	v_mul_f32_e32 v45, 0xbfb8aa3b, v40
	v_exp_f32_e32 v45, v45
	v_fma_f32 v38, -v48, v44, v38
	v_div_fmas_f32 v38, v38, v49, v44
	v_div_fixup_f32 v38, v38, v47, v39
	v_add_f32_e32 v45, 1.0, v45
	v_div_scale_f32 v46, s[52:53], v45, v45, v40
	v_rcp_f32_e32 v48, v46
	v_mul_f32_e32 v35, v38, v35
	v_mul_f32_e32 v38, 0xbfb8aa3b, v41
	v_exp_f32_e32 v38, v38
	v_cvt_pk_bf16_f32 v44, v34, v35
	v_fma_f32 v34, -v46, v48, 1.0
	v_fmac_f32_e32 v48, v34, v48
	v_div_scale_f32 v34, vcc, v40, v45, v40
	v_mul_f32_e32 v35, v34, v48
	v_fma_f32 v39, -v46, v35, v34
	v_add_f32_e32 v38, 1.0, v38
	v_fmac_f32_e32 v35, v39, v48
	v_div_scale_f32 v39, s[52:53], v38, v38, v41
	v_fma_f32 v34, -v46, v35, v34
	v_rcp_f32_e32 v46, v39
	v_div_fmas_f32 v34, v34, v48, v35
	v_div_fixup_f32 v34, v34, v45, v40
	v_mul_f32_e32 v34, v34, v36
	v_fma_f32 v35, -v39, v46, 1.0
	v_fmac_f32_e32 v46, v35, v46
	v_div_scale_f32 v35, vcc, v41, v38, v41
	v_mul_f32_e32 v36, v35, v46
	v_fma_f32 v40, -v39, v36, v35
	v_fmac_f32_e32 v36, v40, v46
	v_fma_f32 v35, -v39, v36, v35
	v_div_fmas_f32 v35, v35, v46, v36
	v_mul_f32_e32 v36, 0xbfb8aa3b, v30
	v_exp_f32_e32 v36, v36
	v_div_fixup_f32 v35, v35, v38, v41
	v_mul_f32_e32 v35, v35, v37
	v_cvt_pk_bf16_f32 v45, v34, v35
	v_add_f32_e32 v36, 1.0, v36
	v_div_scale_f32 v37, s[52:53], v36, v36, v30
	v_rcp_f32_e32 v38, v37
	v_add_u32_e32 v34, 0x90, v150
	v_mad_i64_i32 v[34:35], s[52:53], v34, s63, v[114:115]
	v_lshl_add_u64 v[34:35], v[34:35], 0, v[116:117]
	global_store_dwordx4 v[34:35], v[42:45], off
	v_fma_f32 v34, -v37, v38, 1.0
	v_mul_f32_e32 v39, 0xbfb8aa3b, v31
	v_fmac_f32_e32 v38, v34, v38
	v_div_scale_f32 v34, vcc, v30, v36, v30
	v_exp_f32_e32 v39, v39
	v_mul_f32_e32 v35, v34, v38
	v_fma_f32 v40, -v37, v35, v34
	v_fmac_f32_e32 v35, v40, v38
	v_fma_f32 v34, -v37, v35, v34
	v_add_f32_e32 v37, 1.0, v39
	v_div_scale_f32 v39, s[52:53], v37, v37, v31
	v_rcp_f32_e32 v40, v39
	v_div_fmas_f32 v34, v34, v38, v35
	v_div_fixup_f32 v30, v34, v36, v30
	v_mul_f32_e32 v26, v30, v26
	v_fma_f32 v30, -v39, v40, 1.0
	v_fmac_f32_e32 v40, v30, v40
	v_div_scale_f32 v30, vcc, v31, v37, v31
	v_mul_f32_e32 v34, v30, v40
	v_fma_f32 v35, -v39, v34, v30
	v_fmac_f32_e32 v34, v35, v40
	v_mul_f32_e32 v35, 0xbfb8aa3b, v32
	v_exp_f32_e32 v35, v35
	v_fma_f32 v30, -v39, v34, v30
	v_div_fmas_f32 v30, v30, v40, v34
	v_div_fixup_f32 v30, v30, v37, v31
	v_add_f32_e32 v34, 1.0, v35
	v_div_scale_f32 v35, s[52:53], v34, v34, v32
	v_rcp_f32_e32 v36, v35
	v_mul_f32_e32 v27, v30, v27
	v_mul_f32_e32 v31, 0xbfb8aa3b, v33
	v_cvt_pk_bf16_f32 v26, v26, v27
	v_fma_f32 v27, -v35, v36, 1.0
	v_exp_f32_e32 v31, v31
	v_fmac_f32_e32 v36, v27, v36
	v_div_scale_f32 v27, vcc, v32, v34, v32
	v_mul_f32_e32 v30, v27, v36
	v_fma_f32 v37, -v35, v30, v27
	v_fmac_f32_e32 v30, v37, v36
	v_add_f32_e32 v31, 1.0, v31
	v_fma_f32 v27, -v35, v30, v27
	v_div_scale_f32 v35, s[52:53], v31, v31, v33
	v_rcp_f32_e32 v37, v35
	v_div_fmas_f32 v27, v27, v36, v30
	v_div_fixup_f32 v27, v27, v34, v32
	v_mul_f32_e32 v27, v27, v28
	v_fma_f32 v28, -v35, v37, 1.0
	v_fmac_f32_e32 v37, v28, v37
	v_div_scale_f32 v28, vcc, v33, v31, v33
	v_mul_f32_e32 v30, v28, v37
	v_fma_f32 v32, -v35, v30, v28
	v_fmac_f32_e32 v30, v32, v37
	v_mul_f32_e32 v32, 0xbfb8aa3b, v22
	v_exp_f32_e32 v32, v32
	v_fma_f32 v28, -v35, v30, v28
	v_div_fmas_f32 v28, v28, v37, v30
	v_div_fixup_f32 v28, v28, v31, v33
	v_add_f32_e32 v30, 1.0, v32
	v_div_scale_f32 v32, s[52:53], v30, v30, v22
	v_rcp_f32_e32 v34, v32
	v_mul_f32_e32 v28, v28, v29
	v_mul_f32_e32 v31, 0xbfb8aa3b, v23
	v_cvt_pk_bf16_f32 v27, v27, v28
	v_fma_f32 v28, -v32, v34, 1.0
	v_exp_f32_e32 v31, v31
	v_fmac_f32_e32 v34, v28, v34
	v_div_scale_f32 v28, vcc, v22, v30, v22
	v_mul_f32_e32 v29, v28, v34
	v_fma_f32 v33, -v32, v29, v28
	v_fmac_f32_e32 v29, v33, v34
	v_add_f32_e32 v31, 1.0, v31
	v_fma_f32 v28, -v32, v29, v28
	v_div_scale_f32 v32, s[52:53], v31, v31, v23
	v_rcp_f32_e32 v33, v32
	v_div_fmas_f32 v28, v28, v34, v29
	v_div_fixup_f32 v22, v28, v30, v22
	v_mul_f32_e32 v18, v22, v18
	v_fma_f32 v22, -v32, v33, 1.0
	v_fmac_f32_e32 v33, v22, v33
	v_div_scale_f32 v22, vcc, v23, v31, v23
	v_mul_f32_e32 v28, v22, v33
	v_fma_f32 v29, -v32, v28, v22
	v_fmac_f32_e32 v28, v29, v33
	v_mul_f32_e32 v29, 0xbfb8aa3b, v24
	v_exp_f32_e32 v29, v29
	v_fma_f32 v22, -v32, v28, v22
	v_div_fmas_f32 v22, v22, v33, v28
	v_div_fixup_f32 v22, v22, v31, v23
	v_add_f32_e32 v29, 1.0, v29
	v_div_scale_f32 v30, s[52:53], v29, v29, v24
	v_rcp_f32_e32 v32, v30
	v_mul_f32_e32 v19, v22, v19
	v_mul_f32_e32 v22, 0xbfb8aa3b, v25
	v_exp_f32_e32 v22, v22
	v_cvt_pk_bf16_f32 v28, v18, v19
	v_fma_f32 v18, -v30, v32, 1.0
	v_fmac_f32_e32 v32, v18, v32
	v_div_scale_f32 v18, vcc, v24, v29, v24
	v_mul_f32_e32 v19, v18, v32
	v_fma_f32 v23, -v30, v19, v18
	v_add_f32_e32 v22, 1.0, v22
	v_fmac_f32_e32 v19, v23, v32
	v_div_scale_f32 v23, s[52:53], v22, v22, v25
	v_fma_f32 v18, -v30, v19, v18
	v_rcp_f32_e32 v30, v23
	v_div_fmas_f32 v18, v18, v32, v19
	v_div_fixup_f32 v18, v18, v29, v24
	v_mul_f32_e32 v18, v18, v20
	v_fma_f32 v19, -v23, v30, 1.0
	v_fmac_f32_e32 v30, v19, v30
	v_div_scale_f32 v19, vcc, v25, v22, v25
	v_mul_f32_e32 v20, v19, v30
	v_fma_f32 v24, -v23, v20, v19
	v_fmac_f32_e32 v20, v24, v30
	v_fma_f32 v19, -v23, v20, v19
	v_div_fmas_f32 v19, v19, v30, v20
	v_mul_f32_e32 v20, 0xbfb8aa3b, v14
	v_exp_f32_e32 v20, v20
	v_div_fixup_f32 v19, v19, v22, v25
	v_mul_f32_e32 v19, v19, v21
	v_cvt_pk_bf16_f32 v29, v18, v19
	v_add_f32_e32 v20, 1.0, v20
	v_div_scale_f32 v21, s[52:53], v20, v20, v14
	v_rcp_f32_e32 v22, v21
	v_add_u32_e32 v18, 0xa0, v150
	v_mad_i64_i32 v[18:19], s[52:53], v18, s63, v[114:115]
	v_lshl_add_u64 v[18:19], v[18:19], 0, v[116:117]
	global_store_dwordx4 v[18:19], v[26:29], off
	v_fma_f32 v18, -v21, v22, 1.0
	v_mul_f32_e32 v23, 0xbfb8aa3b, v15
	v_fmac_f32_e32 v22, v18, v22
	v_div_scale_f32 v18, vcc, v14, v20, v14
	v_exp_f32_e32 v23, v23
	v_mul_f32_e32 v19, v18, v22
	v_fma_f32 v24, -v21, v19, v18
	v_fmac_f32_e32 v19, v24, v22
	v_fma_f32 v18, -v21, v19, v18
	v_add_f32_e32 v21, 1.0, v23
	v_div_scale_f32 v23, s[52:53], v21, v21, v15
	v_rcp_f32_e32 v24, v23
	v_div_fmas_f32 v18, v18, v22, v19
	v_div_fixup_f32 v14, v18, v20, v14
	v_mul_f32_e32 v10, v14, v10
	v_fma_f32 v14, -v23, v24, 1.0
	v_fmac_f32_e32 v24, v14, v24
	v_div_scale_f32 v14, vcc, v15, v21, v15
	v_mul_f32_e32 v18, v14, v24
	v_fma_f32 v19, -v23, v18, v14
	v_fmac_f32_e32 v18, v19, v24
	v_mul_f32_e32 v19, 0xbfb8aa3b, v16
	v_exp_f32_e32 v19, v19
	v_fma_f32 v14, -v23, v18, v14
	v_div_fmas_f32 v14, v14, v24, v18
	v_div_fixup_f32 v14, v14, v21, v15
	v_add_f32_e32 v18, 1.0, v19
	v_div_scale_f32 v19, s[52:53], v18, v18, v16
	v_rcp_f32_e32 v20, v19
	v_mul_f32_e32 v11, v14, v11
	v_mul_f32_e32 v15, 0xbfb8aa3b, v17
	v_cvt_pk_bf16_f32 v10, v10, v11
	v_fma_f32 v11, -v19, v20, 1.0
	v_exp_f32_e32 v15, v15
	v_fmac_f32_e32 v20, v11, v20
	v_div_scale_f32 v11, vcc, v16, v18, v16
	v_mul_f32_e32 v14, v11, v20
	v_fma_f32 v21, -v19, v14, v11
	v_fmac_f32_e32 v14, v21, v20
	v_add_f32_e32 v15, 1.0, v15
	v_fma_f32 v11, -v19, v14, v11
	v_div_scale_f32 v19, s[52:53], v15, v15, v17
	v_rcp_f32_e32 v21, v19
	v_div_fmas_f32 v11, v11, v20, v14
	v_div_fixup_f32 v11, v11, v18, v16
	v_mul_f32_e32 v11, v11, v12
	v_fma_f32 v12, -v19, v21, 1.0
	v_fmac_f32_e32 v21, v12, v21
	v_div_scale_f32 v12, vcc, v17, v15, v17
	v_mul_f32_e32 v14, v12, v21
	v_fma_f32 v16, -v19, v14, v12
	v_fmac_f32_e32 v14, v16, v21
	v_mul_f32_e32 v16, 0xbfb8aa3b, v6
	v_exp_f32_e32 v16, v16
	v_fma_f32 v12, -v19, v14, v12
	v_div_fmas_f32 v12, v12, v21, v14
	v_div_fixup_f32 v12, v12, v15, v17
	v_add_f32_e32 v14, 1.0, v16
	v_div_scale_f32 v16, s[52:53], v14, v14, v6
	v_rcp_f32_e32 v18, v16
	v_mul_f32_e32 v12, v12, v13
	v_mul_f32_e32 v15, 0xbfb8aa3b, v7
	v_cvt_pk_bf16_f32 v11, v11, v12
	v_fma_f32 v12, -v16, v18, 1.0
	v_exp_f32_e32 v15, v15
	v_fmac_f32_e32 v18, v12, v18
	v_div_scale_f32 v12, vcc, v6, v14, v6
	v_mul_f32_e32 v13, v12, v18
	v_fma_f32 v17, -v16, v13, v12
	v_fmac_f32_e32 v13, v17, v18
	v_add_f32_e32 v15, 1.0, v15
	v_fma_f32 v12, -v16, v13, v12
	v_div_scale_f32 v16, s[52:53], v15, v15, v7
	v_rcp_f32_e32 v17, v16
	v_div_fmas_f32 v12, v12, v18, v13
	v_div_fixup_f32 v6, v12, v14, v6
	v_mul_f32_e32 v2, v6, v2
	v_fma_f32 v6, -v16, v17, 1.0
	v_fmac_f32_e32 v17, v6, v17
	v_div_scale_f32 v6, vcc, v7, v15, v7
	v_mul_f32_e32 v12, v6, v17
	v_fma_f32 v13, -v16, v12, v6
	v_fmac_f32_e32 v12, v13, v17
	v_mul_f32_e32 v13, 0xbfb8aa3b, v8
	v_exp_f32_e32 v13, v13
	v_fma_f32 v6, -v16, v12, v6
	v_div_fmas_f32 v6, v6, v17, v12
	v_div_fixup_f32 v6, v6, v15, v7
	v_add_f32_e32 v13, 1.0, v13
	v_div_scale_f32 v14, s[52:53], v13, v13, v8
	v_rcp_f32_e32 v16, v14
	v_mul_f32_e32 v3, v6, v3
	v_mul_f32_e32 v6, 0xbfb8aa3b, v9
	v_exp_f32_e32 v6, v6
	v_cvt_pk_bf16_f32 v12, v2, v3
	v_fma_f32 v2, -v14, v16, 1.0
	v_fmac_f32_e32 v16, v2, v16
	v_div_scale_f32 v2, vcc, v8, v13, v8
	v_mul_f32_e32 v3, v2, v16
	v_fma_f32 v7, -v14, v3, v2
	v_add_f32_e32 v6, 1.0, v6
	v_fmac_f32_e32 v3, v7, v16
	v_div_scale_f32 v7, s[52:53], v6, v6, v9
	v_fma_f32 v2, -v14, v3, v2
	v_rcp_f32_e32 v14, v7
	v_div_fmas_f32 v2, v2, v16, v3
	v_div_fixup_f32 v2, v2, v13, v8
	v_mul_f32_e32 v2, v2, v4
	v_fma_f32 v3, -v7, v14, 1.0
	v_fmac_f32_e32 v14, v3, v14
	v_div_scale_f32 v3, vcc, v9, v6, v9
	v_mul_f32_e32 v4, v3, v14
	v_fma_f32 v8, -v7, v4, v3
	v_fmac_f32_e32 v4, v8, v14
	v_fma_f32 v3, -v7, v4, v3
	v_div_fmas_f32 v3, v3, v14, v4
	v_div_fixup_f32 v3, v3, v6, v9
	v_mul_f32_e32 v3, v3, v5
	v_cvt_pk_bf16_f32 v13, v2, v3
	v_add_u32_e32 v2, 0xb0, v150
	v_mad_i64_i32 v[2:3], s[52:53], v2, s63, v[114:115]
	v_lshl_add_u64 v[2:3], v[2:3], 0, v[116:117]
	s_mov_b64 s[52:53], -1
	s_and_b64 vcc, exec, s[48:49]
	global_store_dwordx4 v[2:3], v[10:13], off
	s_cbranch_vccz .LBB0_3459
	s_andn2_b64 vcc, exec, s[6:7]
	s_cbranch_vccnz .LBB0_3458
	s_barrier
	s_branch .LBB0_3458

.LBB0_3487:
	s_lshl_b32 s4, s30, 2
	s_add_u32 s4, s38, s4
	s_addc_u32 s5, s39, 0
	s_add_u32 s10, s4, 0x16000000
	s_addc_u32 s11, s5, 0
	s_mov_b32 s7, 0
	v_add_u32_e32 v130, 0x4000, v140
	s_movk_i32 s4, 0x3000
	v_mov_b64_e32 v[134:135], s[10:11]
	s_lshl_b32 s6, s3, 8
	v_mad_i64_i32 v[136:137], s[10:11], v130, s4, v[134:135]
	s_lshl_b64 s[6:7], s[6:7], 2
	v_lshl_add_u64 v[136:137], v[136:137], 0, s[6:7]
	v_mov_b32_e32 v133, 0
	v_lshl_add_u64 v[136:137], v[136:137], 0, v[132:133]
	global_store_dwordx4 v[136:137], v[126:129], off
	global_store_dwordx4 v[136:137], v[122:125], off offset:64
	global_store_dwordx4 v[136:137], v[106:109], off offset:512
	global_store_dwordx4 v[136:137], v[98:101], off offset:576
	s_ashr_i32 s5, s25, 6
	v_and_b32_e32 v131, 63, v1
	v_add_u32_e32 v98, 0x4010, v140
	v_mad_i64_i32 v[98:99], s[10:11], v98, s4, v[134:135]
	v_lshl_add_u64 v[98:99], v[98:99], 0, s[6:7]
	v_lshl_add_u64 v[98:99], v[98:99], 0, v[132:133]
	global_store_dwordx4 v[98:99], v[118:121], off
	global_store_dwordx4 v[98:99], v[114:117], off offset:64
	global_store_dwordx4 v[98:99], v[90:93], off offset:512
	global_store_dwordx4 v[98:99], v[82:85], off offset:576
	s_add_i32 s8, s5, s2
	s_nop 0
	v_add_u32_e32 v82, 0x4020, v140
	v_mad_i64_i32 v[82:83], s[10:11], v82, s4, v[134:135]
	v_lshl_add_u64 v[82:83], v[82:83], 0, s[6:7]
	v_lshl_add_u64 v[82:83], v[82:83], 0, v[132:133]
	global_store_dwordx4 v[82:83], v[110:113], off
	global_store_dwordx4 v[82:83], v[102:105], off offset:64
	global_store_dwordx4 v[82:83], v[78:81], off offset:512
	global_store_dwordx4 v[82:83], v[74:77], off offset:576
	s_nop 1
	v_add_u32_e32 v74, 0x4030, v140
	v_mad_i64_i32 v[74:75], s[10:11], v74, s4, v[134:135]
	v_lshl_add_u64 v[74:75], v[74:75], 0, s[6:7]
	v_lshl_add_u64 v[74:75], v[74:75], 0, v[132:133]
	global_store_dwordx4 v[74:75], v[94:97], off
	global_store_dwordx4 v[74:75], v[86:89], off offset:64
	global_store_dwordx4 v[74:75], v[70:73], off offset:512
	global_store_dwordx4 v[74:75], v[66:69], off offset:576
	s_nop 1
	v_add_u32_e32 v66, 0x4080, v140
	v_mad_i64_i32 v[66:67], s[10:11], v66, s4, v[134:135]
	v_lshl_add_u64 v[66:67], v[66:67], 0, s[6:7]
	v_lshl_add_u64 v[66:67], v[66:67], 0, v[132:133]
	global_store_dwordx4 v[66:67], v[62:65], off
	global_store_dwordx4 v[66:67], v[58:61], off offset:64
	global_store_dwordx4 v[66:67], v[42:45], off offset:512
	global_store_dwordx4 v[66:67], v[34:37], off offset:576
	s_nop 1
	v_add_u32_e32 v34, 0x4090, v140
	v_mad_i64_i32 v[34:35], s[10:11], v34, s4, v[134:135]
	v_lshl_add_u64 v[34:35], v[34:35], 0, s[6:7]
	v_lshl_add_u64 v[34:35], v[34:35], 0, v[132:133]
	global_store_dwordx4 v[34:35], v[54:57], off
	global_store_dwordx4 v[34:35], v[50:53], off offset:64
	global_store_dwordx4 v[34:35], v[26:29], off offset:512
	global_store_dwordx4 v[34:35], v[18:21], off offset:576
	s_nop 1
	v_add_u32_e32 v18, 0x40a0, v140
	v_mad_i64_i32 v[18:19], s[10:11], v18, s4, v[134:135]
	v_lshl_add_u64 v[18:19], v[18:19], 0, s[6:7]
	v_lshl_add_u64 v[18:19], v[18:19], 0, v[132:133]
	global_store_dwordx4 v[18:19], v[46:49], off
	global_store_dwordx4 v[18:19], v[38:41], off offset:64
	global_store_dwordx4 v[18:19], v[14:17], off offset:512
	global_store_dwordx4 v[18:19], v[10:13], off offset:576
	s_nop 1
	v_add_u32_e32 v10, 0x40b0, v140
	v_mad_i64_i32 v[10:11], s[10:11], v10, s4, v[134:135]
	v_lshl_add_u64 v[10:11], v[10:11], 0, s[6:7]
	v_lshl_add_u64 v[10:11], v[10:11], 0, v[132:133]
	global_store_dwordx4 v[10:11], v[30:33], off
	global_store_dwordx4 v[10:11], v[22:25], off offset:64
	global_store_dwordx4 v[10:11], v[6:9], off offset:512
	global_store_dwordx4 v[10:11], v[2:5], off offset:576
	s_waitcnt vmcnt(0)
	s_barrier

.LBB0_3609:
	s_or_b64 exec, exec, s[10:11]
	v_mov_b32_e32 v130, v0
	v_mov_b64_e32 v[2:3], s[0:1]
	s_barrier
	global_load_dwordx2 v[2:3], v[2:3], off offset:88 sc0 sc1
	s_waitcnt vmcnt(0)
	v_readfirstlane_b32 s6, v130
	s_ashr_i32 s96, s6, 6
	s_add_i32 s12, s96, s2
	s_cmp_gt_i32 s96, 15
	v_and_b32_e32 v132, 63, v130
	s_cbranch_scc1 .LBB0_3612
	v_mov_b32_e32 v91, 0
	v_lshlrev_b32_e32 v90, 4, v132
	s_waitcnt lgkmcnt(0)
	v_lshl_add_u64 v[2:3], v[2:3], 0, v[90:91]
	s_movk_i32 s2, 0x4000
	v_add_co_u32_e32 v18, vcc, s2, v2
	v_mbcnt_lo_u32_b32 v1, -1, 0
	s_nop 0
	v_addc_co_u32_e32 v19, vcc, 0, v3, vcc
	global_load_dwordx4 v[2:5], v[18:19], off
	global_load_dwordx4 v[6:9], v[18:19], off offset:1024
	global_load_dwordx4 v[10:13], v[18:19], off offset:2048
	global_load_dwordx4 v[14:17], v[18:19], off offset:3072
	v_mbcnt_hi_u32_b32 v18, -1, v1
	v_and_b32_e32 v1, 64, v18
	v_add_u32_e32 v19, 64, v1
	v_xor_b32_e32 v1, 1, v18
	v_cmp_lt_i32_e32 vcc, v1, v19
	v_xor_b32_e32 v20, 2, v18
	s_lshl_b32 s7, s26, 8
	v_cndmask_b32_e32 v1, v18, v1, vcc
	v_cmp_lt_i32_e32 vcc, v20, v19
	s_lshl_b32 s2, s5, 6
	s_add_i32 s8, s7, s2
	v_cndmask_b32_e32 v20, v18, v20, vcc
	v_lshlrev_b32_e32 v131, 2, v20
	v_xor_b32_e32 v20, 4, v18
	v_cmp_lt_i32_e32 vcc, v20, v19
	s_lshl_b32 s9, s96, 2
	s_add_i32 s6, s9, s8
	v_cndmask_b32_e32 v20, v18, v20, vcc
	v_lshlrev_b32_e32 v133, 2, v20
	v_xor_b32_e32 v20, 8, v18
	v_cmp_lt_i32_e32 vcc, v20, v19
	s_add_u32 s2, s38, 0x5803000
	s_addc_u32 s5, s39, 0
	v_cndmask_b32_e32 v20, v18, v20, vcc
	v_lshlrev_b32_e32 v152, 2, v20
	v_xor_b32_e32 v20, 16, v18
	v_cmp_lt_i32_e32 vcc, v20, v19
	s_lshl_b32 s4, s4, 6
	s_add_i32 s4, s7, s4
	v_cndmask_b32_e32 v20, v18, v20, vcc
	v_lshlrev_b32_e32 v153, 2, v20
	v_xor_b32_e32 v20, 32, v18
	v_cmp_lt_i32_e32 vcc, v20, v19
	s_add_i32 s4, s4, s9
	s_lshl_b32 s3, s3, 6
	v_cndmask_b32_e32 v18, v18, v20, vcc
	v_lshlrev_b32_e32 v154, 2, v18
	v_lshlrev_b32_e32 v18, 2, v132
	s_ashr_i32 s7, s6, 31
	v_or_b32_e32 v20, 0x100, v18
	v_or_b32_e32 v22, 0x200, v18
	v_or_b32_e32 v24, 0x300, v18
	s_sub_i32 s3, s4, s3
	s_lshl_b64 s[10:11], s[6:7], 11
	s_lshl_b64 s[6:7], s[6:7], 12
	v_lshlrev_b32_e32 v1, 2, v1
	s_or_b32 s13, s8, 32
	s_sub_i32 s8, s3, 32
	v_lshl_or_b32 v92, v132, 3, s10
	v_mov_b32_e32 v93, s11
	v_or_b32_e32 v94, s6, v90
	v_mov_b32_e32 v95, s7
	v_mov_b32_e32 v155, 0x358637bd
	s_mov_b32 s3, 0xf800000
	v_mov_b32_e32 v156, 0x260
	v_lshlrev_b32_e32 v90, 2, v18
	s_movk_i32 s4, 0x7fff
	s_mov_b32 s22, 0xffff0000
	s_mov_b32 s23, 0xba00000
	v_lshlrev_b32_e32 v96, 2, v20
	v_mov_b32_e32 v97, v91
	v_lshlrev_b32_e32 v98, 2, v22
	v_mov_b32_e32 v99, v91
	v_lshlrev_b32_e32 v100, 2, v24
	v_mov_b32_e32 v101, v91
	s_mov_b32 s24, 0xba01000
	s_mov_b64 s[14:15], 0x10000
	s_mov_b64 s[18:19], 0x20000
.LBB0_3611:
	v_lshl_add_u64 v[18:19], s[38:39], 0, v[94:95]
	v_lshl_add_u64 v[22:23], s[38:39], 0, v[92:93]
	v_add_co_u32_e32 v20, vcc, 0x7800000, v18
	v_add_co_u32_e64 v102, s[6:7], s23, v22
	s_nop 0
	v_addc_co_u32_e32 v21, vcc, 0, v19, vcc
	v_addc_co_u32_e64 v103, s[6:7], 0, v23, s[6:7]
	v_add_co_u32_e64 v104, s[6:7], s24, v22
	v_add_co_u32_e32 v22, vcc, 0x7801000, v18
	s_nop 0
	v_addc_co_u32_e64 v105, s[6:7], 0, v23, s[6:7]
	global_load_dwordx4 v[78:81], v[20:21], off
	global_load_dwordx4 v[74:77], v[20:21], off offset:1024
	global_load_dwordx4 v[70:73], v[20:21], off offset:2048
	global_load_dwordx4 v[66:69], v[20:21], off offset:3072
	v_addc_co_u32_e32 v23, vcc, 0, v19, vcc
	v_add_co_u32_e32 v20, vcc, 0x7802000, v18
	global_load_dwordx4 v[62:65], v[22:23], off
	global_load_dwordx4 v[58:61], v[22:23], off offset:1024
	global_load_dwordx4 v[54:57], v[22:23], off offset:2048
	global_load_dwordx4 v[50:53], v[22:23], off offset:3072
	v_addc_co_u32_e32 v21, vcc, 0, v19, vcc
	v_add_co_u32_e32 v82, vcc, 0x7803000, v18
	global_load_dwordx4 v[46:49], v[20:21], off
	global_load_dwordx4 v[42:45], v[20:21], off offset:1024
	global_load_dwordx4 v[38:41], v[20:21], off offset:2048
	global_load_dwordx4 v[34:37], v[20:21], off offset:3072
	v_addc_co_u32_e32 v83, vcc, 0, v19, vcc
	global_load_dwordx4 v[30:33], v[82:83], off
	global_load_dwordx4 v[26:29], v[82:83], off offset:1024
	global_load_dwordx4 v[22:25], v[82:83], off offset:2048
	global_load_dwordx4 v[18:21], v[82:83], off offset:3072
	s_add_i32 s25, s8, 32
	s_add_i32 s10, s8, 0xffffc022
	s_ashr_i32 s9, s25, 13
	s_cmpk_lt_i32 s25, 0x4000
	s_cselect_b32 s6, s9, s10
	s_addk_i32 s6, 0x82
	s_mul_hi_i32 s7, s6, 0x9000
	s_mul_i32 s6, s6, 0x9000
	s_add_u32 s6, s2, s6
	s_addc_u32 s7, s5, s7
	s_add_u32 s10, s6, 0x1000
	s_addc_u32 s11, s7, 0
	v_lshl_add_u64 v[124:125], s[6:7], 0, v[90:91]
	v_lshl_add_u64 v[86:87], s[10:11], 0, v[90:91]
	global_load_dwordx4 v[82:85], v[124:125], off
	s_add_i32 s6, s8, 0xffffc023
	global_load_dwordx4 v[86:89], v[86:87], off
	s_cmpk_lt_i32 s25, 0x3fff
	s_cselect_b32 s6, s9, s6
	s_addk_i32 s6, 0x82
	s_mul_hi_i32 s7, s6, 0x9000
	s_mul_i32 s6, s6, 0x9000
	s_add_u32 s6, s2, s6
	s_addc_u32 s7, s5, s7
	v_lshl_add_u64 v[138:139], s[10:11], 0, v[96:97]
	v_lshl_add_u64 v[134:135], s[10:11], 0, v[98:99]
	v_lshl_add_u64 v[128:129], s[10:11], 0, v[100:101]
	s_add_u32 s10, s6, 0x1000
	v_lshl_add_u64 v[110:111], s[6:7], 0, v[90:91]
	s_addc_u32 s11, s7, 0
	s_add_i32 s6, s8, 0xffffc024
	s_cmpk_lt_i32 s25, 0x3ffe
	s_cselect_b32 s6, s9, s6
	s_addk_i32 s6, 0x82
	s_mul_hi_i32 s7, s6, 0x9000
	s_mul_i32 s6, s6, 0x9000
	v_lshl_add_u64 v[126:127], s[10:11], 0, v[90:91]
	v_lshl_add_u64 v[120:121], s[10:11], 0, v[96:97]
	v_lshl_add_u64 v[116:117], s[10:11], 0, v[98:99]
	v_lshl_add_u64 v[112:113], s[10:11], 0, v[100:101]
	s_add_u32 s10, s2, s6
	s_addc_u32 s11, s5, s7
	s_add_u32 s6, s10, 0x1000
	s_addc_u32 s7, s11, 0
	s_addk_i32 s8, 0xc025
	s_cmpk_lt_i32 s25, 0x3ffd
	v_lshl_add_u64 v[142:143], s[6:7], 0, v[90:91]
	v_lshl_add_u64 v[140:141], s[6:7], 0, v[96:97]
	v_lshl_add_u64 v[136:137], s[6:7], 0, v[98:99]
	v_lshl_add_u64 v[122:123], s[6:7], 0, v[100:101]
	s_cselect_b32 s6, s9, s8
	s_addk_i32 s6, 0x82
	s_mul_hi_i32 s7, s6, 0x9000
	s_mul_i32 s6, s6, 0x9000
	s_add_u32 s6, s2, s6
	s_addc_u32 s7, s5, s7
	s_add_u32 s20, s6, 0x1000
	v_lshl_add_u64 v[106:107], s[6:7], 0, v[90:91]
	s_addc_u32 s21, s7, 0
	v_lshl_add_u64 v[108:109], s[10:11], 0, v[90:91]
	v_lshl_add_u64 v[118:119], s[20:21], 0, v[90:91]
	v_lshl_add_u64 v[114:115], s[20:21], 0, v[96:97]
	v_lshl_add_u64 v[92:93], v[92:93], 0, s[14:15]
	s_waitcnt vmcnt(0) lgkmcnt(0)
	v_pk_mul_f32 v[144:145], v[80:81], v[80:81]
	v_pk_mul_f32 v[146:147], v[78:79], v[78:79]
	v_pk_mul_f32 v[148:149], v[76:77], v[76:77]
	v_pk_mul_f32 v[150:151], v[74:75], v[74:75]
	v_mul_f32_e32 v158, v71, v71
	v_mul_f32_e32 v160, v73, v73
	v_mul_f32_e32 v171, v68, v68
	v_mul_f32_e32 v173, v69, v69
	v_pk_mov_b32 v[162:163], v[146:147], v[144:145] op_sel:[1,0]
	v_mov_b32_e32 v147, v145
	v_pk_mov_b32 v[144:145], v[150:151], v[148:149] op_sel:[1,0]
	v_mov_b32_e32 v151, v149
	v_pk_fma_f32 v[148:149], v[70:71], v[70:71], v[158:159] op_sel_hi:[1,1,0]
	v_pk_fma_f32 v[158:159], v[72:73], v[72:73], v[160:161] op_sel_hi:[1,1,0]
	v_pk_mul_f32 v[160:161], v[64:65], v[64:65]
	v_pk_mul_f32 v[164:165], v[62:63], v[62:63]
	v_pk_mul_f32 v[166:167], v[60:61], v[60:61]
	v_pk_mul_f32 v[168:169], v[58:59], v[58:59]
	v_mul_f32_e32 v170, v55, v55
	v_mul_f32_e32 v172, v57, v57
	v_pk_add_f32 v[146:147], v[162:163], v[146:147]
	v_pk_add_f32 v[144:145], v[144:145], v[150:151]
	v_mov_b32_e32 v149, v171
	v_mov_b32_e32 v159, v173
	v_pk_mov_b32 v[150:151], v[164:165], v[160:161] op_sel:[1,0]
	v_mov_b32_e32 v165, v161
	v_pk_mov_b32 v[160:161], v[168:169], v[166:167] op_sel:[1,0]
	v_mov_b32_e32 v169, v167
	v_pk_fma_f32 v[162:163], v[54:55], v[54:55], v[170:171] op_sel_hi:[1,1,0]
	v_pk_fma_f32 v[166:167], v[56:57], v[56:57], v[172:173] op_sel_hi:[1,1,0]
	v_pk_mul_f32 v[170:171], v[48:49], v[48:49]
	v_pk_mul_f32 v[172:173], v[46:47], v[46:47]
	v_pk_mul_f32 v[174:175], v[44:45], v[44:45]
	v_pk_mul_f32 v[176:177], v[42:43], v[42:43]
	v_mul_f32_e32 v157, v66, v66
	v_mul_f32_e32 v181, v67, v67
	v_mul_f32_e32 v179, v52, v52
	v_mul_f32_e32 v186, v53, v53
	v_mul_f32_e32 v178, v39, v39
	v_mul_f32_e32 v180, v41, v41
	v_pk_add_f32 v[182:183], v[146:147], v[146:147] op_sel:[0,1] op_sel_hi:[1,0]
	v_pk_add_f32 v[184:185], v[144:145], v[144:145] op_sel:[0,1] op_sel_hi:[1,0]
	v_pk_add_f32 v[158:159], v[148:149], v[158:159]
	v_pk_add_f32 v[144:145], v[150:151], v[164:165]
	v_pk_add_f32 v[146:147], v[160:161], v[168:169]
	v_pk_mov_b32 v[148:149], v[172:173], v[170:171] op_sel:[1,0]
	v_mov_b32_e32 v173, v171
	v_pk_mov_b32 v[150:151], v[176:177], v[174:175] op_sel:[1,0]
	v_mov_b32_e32 v177, v175
	v_mul_f32_e32 v187, v50, v50
	v_mul_f32_e32 v192, v51, v51
	v_mul_f32_e32 v195, v36, v36
	v_mul_f32_e32 v196, v37, v37
	v_mov_b32_e32 v163, v179
	v_mov_b32_e32 v167, v186
	v_pk_fma_f32 v[160:161], v[38:39], v[38:39], v[178:179] op_sel_hi:[1,1,0]
	v_pk_fma_f32 v[164:165], v[40:41], v[40:41], v[180:181] op_sel_hi:[1,1,0]
	v_pk_mul_f32 v[168:169], v[32:33], v[32:33]
	v_pk_mul_f32 v[170:171], v[30:31], v[30:31]
	v_pk_mul_f32 v[174:175], v[28:29], v[28:29]
	v_pk_mul_f32 v[178:179], v[26:27], v[26:27]
	v_mov_b32_e32 v183, v157
	v_mov_b32_e32 v185, v181
	v_pk_add_f32 v[188:189], v[144:145], v[144:145] op_sel:[0,1] op_sel_hi:[1,0]
	v_pk_add_f32 v[190:191], v[146:147], v[146:147] op_sel:[0,1] op_sel_hi:[1,0]
	v_pk_add_f32 v[148:149], v[148:149], v[172:173]
	v_pk_add_f32 v[150:151], v[150:151], v[176:177]
	v_mul_f32_e32 v193, v34, v34
	v_mul_f32_e32 v194, v35, v35
	v_pk_add_f32 v[162:163], v[162:163], v[166:167]
	v_mov_b32_e32 v161, v195
	v_mov_b32_e32 v165, v196
	v_pk_mov_b32 v[166:167], v[170:171], v[168:169] op_sel:[1,0]
	v_mov_b32_e32 v171, v169
	v_pk_mov_b32 v[168:169], v[178:179], v[174:175] op_sel:[1,0]
	v_mov_b32_e32 v179, v175
	v_pk_add_f32 v[172:173], v[182:183], v[184:185]
	v_mov_b32_e32 v189, v187
	v_mov_b32_e32 v191, v192
	v_pk_add_f32 v[174:175], v[148:149], v[148:149] op_sel:[0,1] op_sel_hi:[1,0]
	v_pk_add_f32 v[176:177], v[150:151], v[150:151] op_sel:[0,1] op_sel_hi:[1,0]
	v_pk_add_f32 v[160:161], v[160:161], v[164:165]
	v_pk_add_f32 v[158:159], v[172:173], v[158:159]
	v_pk_add_f32 v[164:165], v[188:189], v[190:191]
	v_mov_b32_e32 v175, v193
	v_mov_b32_e32 v177, v194
	v_add_f32_e32 v157, v158, v159
	v_pk_add_f32 v[158:159], v[164:165], v[162:163]
	v_pk_add_f32 v[162:163], v[174:175], v[176:177]
	v_add_f32_e32 v164, v158, v159
	v_pk_add_f32 v[158:159], v[162:163], v[160:161]
	ds_bpermute_b32 v160, v1, v157
	ds_bpermute_b32 v161, v1, v164
	v_add_f32_e32 v158, v158, v159
	ds_bpermute_b32 v159, v1, v158
	v_pk_add_f32 v[148:149], v[166:167], v[170:171]
	s_waitcnt lgkmcnt(2)
	v_add_f32_e32 v157, v157, v160
	ds_bpermute_b32 v160, v131, v157
	s_waitcnt lgkmcnt(2)
	v_add_f32_e32 v161, v164, v161
	ds_bpermute_b32 v162, v131, v161
	s_waitcnt lgkmcnt(2)
	v_add_f32_e32 v158, v158, v159
	ds_bpermute_b32 v159, v131, v158
	s_waitcnt lgkmcnt(2)
	v_add_f32_e32 v157, v157, v160
	ds_bpermute_b32 v160, v133, v157
	s_waitcnt lgkmcnt(2)
	v_add_f32_e32 v161, v161, v162
	ds_bpermute_b32 v162, v133, v161
	s_waitcnt lgkmcnt(2)
	v_add_f32_e32 v158, v158, v159
	ds_bpermute_b32 v159, v133, v158
	s_waitcnt lgkmcnt(2)
	v_add_f32_e32 v157, v157, v160
	ds_bpermute_b32 v160, v152, v157
	s_waitcnt lgkmcnt(2)
	v_add_f32_e32 v161, v161, v162
	ds_bpermute_b32 v162, v152, v161
	s_waitcnt lgkmcnt(2)
	v_add_f32_e32 v158, v158, v159
	ds_bpermute_b32 v159, v152, v158
	s_waitcnt lgkmcnt(2)
	v_add_f32_e32 v157, v157, v160
	ds_bpermute_b32 v160, v153, v157
	s_waitcnt lgkmcnt(2)
	v_add_f32_e32 v161, v161, v162
	ds_bpermute_b32 v162, v153, v161
	s_waitcnt lgkmcnt(2)
	v_add_f32_e32 v158, v158, v159
	ds_bpermute_b32 v159, v153, v158
	s_waitcnt lgkmcnt(2)
	v_add_f32_e32 v157, v157, v160
	ds_bpermute_b32 v160, v154, v157
	s_waitcnt lgkmcnt(2)
	v_add_f32_e32 v161, v161, v162
	ds_bpermute_b32 v162, v154, v161
	s_waitcnt lgkmcnt(2)
	v_add_f32_e32 v158, v158, v159
	ds_bpermute_b32 v159, v154, v158
	s_waitcnt lgkmcnt(2)
	v_add_f32_e32 v157, v157, v160
	v_fmamk_f32 v157, v157, 0x3a800000, v155
	s_waitcnt lgkmcnt(1)
	v_add_f32_e32 v160, v161, v162
	v_mul_f32_e32 v161, 0x4f800000, v157
	v_cmp_gt_f32_e32 vcc, s3, v157
	v_fmamk_f32 v160, v160, 0x3a800000, v155
	s_waitcnt lgkmcnt(0)
	v_add_f32_e32 v158, v158, v159
	v_cndmask_b32_e32 v157, v157, v161, vcc
	v_mul_f32_e32 v159, 0x4f800000, v160
	v_cmp_gt_f32_e64 s[6:7], s3, v160
	v_sqrt_f32_e32 v161, v157
	v_fmamk_f32 v158, v158, 0x3a800000, v155
	v_cndmask_b32_e64 v159, v160, v159, s[6:7]
	v_mul_f32_e32 v160, 0x4f800000, v158
	v_cmp_gt_f32_e64 s[8:9], s3, v158
	v_sqrt_f32_e32 v162, v159
	v_add_u32_e32 v163, -1, v161
	v_cndmask_b32_e64 v158, v158, v160, s[8:9]
	v_sqrt_f32_e32 v160, v158
	v_add_u32_e32 v164, 1, v161
	v_fma_f32 v165, -v163, v161, v157
	v_fma_f32 v166, -v164, v161, v157
	v_add_u32_e32 v167, -1, v162
	v_cmp_ge_f32_e64 s[10:11], 0, v165
	v_pk_add_f32 v[150:151], v[168:169], v[178:179]
	v_add_u32_e32 v168, 1, v162
	v_cndmask_b32_e64 v161, v161, v163, s[10:11]
	v_fma_f32 v163, -v167, v162, v159
	v_cmp_lt_f32_e64 s[10:11], 0, v166
	v_fma_f32 v165, -v168, v162, v159
	v_add_u32_e32 v169, -1, v160
	v_cndmask_b32_e64 v161, v161, v164, s[10:11]
	v_cmp_ge_f32_e64 s[10:11], 0, v163
	v_add_u32_e32 v170, 1, v160
	v_fma_f32 v163, -v169, v160, v158
	v_cndmask_b32_e64 v162, v162, v167, s[10:11]
	v_cmp_lt_f32_e64 s[10:11], 0, v165
	v_fma_f32 v164, -v170, v160, v158
	v_mul_f32_e32 v165, 0x37800000, v161
	v_cndmask_b32_e64 v162, v162, v168, s[10:11]
	v_cmp_ge_f32_e64 s[10:11], 0, v163
	v_cndmask_b32_e32 v161, v161, v165, vcc
	v_cmp_class_f32_e32 vcc, v157, v156
	v_cndmask_b32_e64 v160, v160, v169, s[10:11]
	v_cmp_lt_f32_e64 s[10:11], 0, v164
	v_mul_f32_e32 v163, 0x37800000, v162
	v_cndmask_b32_e32 v157, v161, v157, vcc
	v_cndmask_b32_e64 v160, v160, v170, s[10:11]
	v_cndmask_b32_e64 v161, v162, v163, s[6:7]
	v_cmp_class_f32_e32 vcc, v159, v156
	v_mul_f32_e32 v162, 0x37800000, v160
	v_div_scale_f32 v163, s[6:7], v157, v157, 1.0
	v_cndmask_b32_e32 v159, v161, v159, vcc
	v_cndmask_b32_e64 v160, v160, v162, s[8:9]
	v_cmp_class_f32_e32 vcc, v158, v156
	v_rcp_f32_e32 v161, v163
	v_div_scale_f32 v162, s[8:9], v159, v159, 1.0
	v_cndmask_b32_e32 v160, v160, v158, vcc
	v_rcp_f32_e32 v166, v162
	v_div_scale_f32 v167, s[10:11], v160, v160, 1.0
	v_rcp_f32_e32 v169, v167
	v_fma_f32 v158, -v163, v161, 1.0
	v_div_scale_f32 v164, s[6:7], 1.0, v157, 1.0
	v_fmac_f32_e32 v161, v158, v161
	v_fma_f32 v158, -v162, v166, 1.0
	v_mul_f32_e32 v170, v164, v161
	v_div_scale_f32 v165, s[8:9], 1.0, v159, 1.0
	v_fmac_f32_e32 v166, v158, v166
	v_fma_f32 v158, -v167, v169, 1.0
	v_fma_f32 v171, -v163, v170, v164
	v_div_scale_f32 v168, s[10:11], 1.0, v160, 1.0
	v_mul_f32_e32 v172, v165, v166
	v_fmac_f32_e32 v169, v158, v169
	v_fmac_f32_e32 v170, v171, v161
	v_fma_f32 v158, -v162, v172, v165
	v_mul_f32_e32 v171, v168, v169
	v_fma_f32 v163, -v163, v170, v164
	s_mov_b64 vcc, s[6:7]
	v_fmac_f32_e32 v172, v158, v166
	v_fma_f32 v158, -v167, v171, v168
	v_div_fmas_f32 v161, v163, v161, v170
	v_fma_f32 v162, -v162, v172, v165
	v_fmac_f32_e32 v171, v158, v169
	v_div_fixup_f32 v158, v161, v157, 1.0
	s_mov_b64 vcc, s[8:9]
	v_div_fmas_f32 v157, v162, v166, v172
	v_fma_f32 v161, -v167, v171, v168
	v_pk_mul_f32 v[80:81], v[80:81], v[158:159] op_sel_hi:[1,0]
	v_pk_mul_f32 v[78:79], v[78:79], v[158:159] op_sel_hi:[1,0]
	s_mov_b64 vcc, s[10:11]
	v_pk_add_f32 v[88:89], v[88:89], 1.0 op_sel_hi:[1,0]
	v_pk_add_f32 v[86:87], v[86:87], 1.0 op_sel_hi:[1,0]
	v_pk_mul_f32 v[76:77], v[76:77], v[158:159] op_sel_hi:[1,0]
	v_pk_mul_f32 v[74:75], v[74:75], v[158:159] op_sel_hi:[1,0]
	v_pk_mul_f32 v[72:73], v[72:73], v[158:159] op_sel_hi:[1,0]
	v_pk_mul_f32 v[70:71], v[70:71], v[158:159] op_sel_hi:[1,0]
	v_pk_mul_f32 v[68:69], v[68:69], v[158:159] op_sel_hi:[1,0]
	v_pk_mul_f32 v[66:67], v[66:67], v[158:159] op_sel_hi:[1,0]
	v_div_fixup_f32 v158, v157, v159, 1.0
	v_div_fmas_f32 v157, v161, v169, v171
	v_pk_mul_f32 v[78:79], v[78:79], v[2:3]
	v_pk_mul_f32 v[80:81], v[80:81], v[4:5]
	v_pk_mul_f32 v[64:65], v[64:65], v[158:159] op_sel_hi:[1,0]
	v_pk_mul_f32 v[62:63], v[62:63], v[158:159] op_sel_hi:[1,0]
	v_pk_mul_f32 v[60:61], v[60:61], v[158:159] op_sel_hi:[1,0]
	v_pk_mul_f32 v[58:59], v[58:59], v[158:159] op_sel_hi:[1,0]
	v_pk_mul_f32 v[56:57], v[56:57], v[158:159] op_sel_hi:[1,0]
	v_pk_mul_f32 v[54:55], v[54:55], v[158:159] op_sel_hi:[1,0]
	v_pk_mul_f32 v[52:53], v[52:53], v[158:159] op_sel_hi:[1,0]
	v_pk_mul_f32 v[158:159], v[50:51], v[158:159] op_sel_hi:[1,0]
	v_div_fixup_f32 v50, v157, v160, 1.0
	v_pk_fma_f32 v[80:81], v[80:81], v[88:89], v[84:85]
	v_pk_fma_f32 v[78:79], v[78:79], v[86:87], v[82:83]
	v_pk_mul_f32 v[86:87], v[52:53], v[16:17]
	v_pk_mul_f32 v[48:49], v[48:49], v[50:51] op_sel_hi:[1,0]
	v_pk_mul_f32 v[46:47], v[46:47], v[50:51] op_sel_hi:[1,0]
	v_bfe_u32 v51, v78, 16, 1
	v_bfe_u32 v53, v80, 16, 1
	v_pk_mul_f32 v[82:83], v[54:55], v[10:11]
	v_pk_mul_f32 v[84:85], v[158:159], v[14:15]
	v_bfe_u32 v52, v79, 16, 1
	v_bfe_u32 v54, v81, 16, 1
	v_pk_mul_f32 v[88:89], v[46:47], v[2:3]
	v_pk_mul_f32 v[158:159], v[48:49], v[4:5]
	v_add3_u32 v46, v78, v51, s4
	v_add3_u32 v48, v80, v53, s4
	v_add3_u32 v47, v79, v52, s4
	v_add3_u32 v49, v81, v54, s4
	v_lshrrev_b32_e32 v46, 16, v46
	v_lshrrev_b32_e32 v48, 16, v48
	v_and_or_b32 v46, v47, s22, v46
	v_and_or_b32 v47, v49, s22, v48
	global_store_dwordx2 v[102:103], v[46:47], off
	global_load_dwordx4 v[46:49], v[138:139], off
	s_nop 0
	global_load_dwordx4 v[52:55], v[124:125], off offset:1024
	v_pk_mul_f32 v[74:75], v[74:75], v[6:7]
	v_pk_mul_f32 v[76:77], v[76:77], v[8:9]
	v_pk_mul_f32 v[70:71], v[70:71], v[10:11]
	v_pk_mul_f32 v[72:73], v[72:73], v[12:13]
	v_pk_mul_f32 v[66:67], v[66:67], v[14:15]
	v_pk_mul_f32 v[68:69], v[68:69], v[16:17]
	v_pk_mul_f32 v[62:63], v[62:63], v[2:3]
	v_pk_mul_f32 v[64:65], v[64:65], v[4:5]
	v_pk_mul_f32 v[58:59], v[58:59], v[6:7]
	v_pk_mul_f32 v[60:61], v[60:61], v[8:9]
	v_pk_mul_f32 v[56:57], v[56:57], v[12:13]
	v_mul_f32_e32 v180, v23, v23
	v_mul_f32_e32 v186, v25, v25
	v_mul_f32_e32 v197, v18, v18
	v_mul_f32_e32 v198, v19, v19
	v_mul_f32_e32 v199, v20, v20
	v_mul_f32_e32 v200, v21, v21
	v_pk_fma_f32 v[144:145], v[22:23], v[22:23], v[180:181] op_sel_hi:[1,1,0]
	v_pk_fma_f32 v[146:147], v[24:25], v[24:25], v[186:187] op_sel_hi:[1,1,0]
	v_mov_b32_e32 v145, v199
	v_mov_b32_e32 v147, v200
	v_lshl_add_u64 v[94:95], v[94:95], 0, s[18:19]
	s_mov_b32 s8, s25
	s_cmp_lt_i32 s25, s13
	s_waitcnt vmcnt(0) lgkmcnt(0)
	v_pk_add_f32 v[48:49], v[48:49], 1.0 op_sel_hi:[1,0]
	v_pk_add_f32 v[46:47], v[46:47], 1.0 op_sel_hi:[1,0]
	v_pk_fma_f32 v[48:49], v[76:77], v[48:49], v[54:55]
	v_pk_fma_f32 v[46:47], v[74:75], v[46:47], v[52:53]
	v_bfe_u32 v53, v48, 16, 1
	v_bfe_u32 v51, v46, 16, 1
	v_bfe_u32 v52, v47, 16, 1
	v_bfe_u32 v54, v49, 16, 1
	v_add3_u32 v46, v46, v51, s4
	v_add3_u32 v48, v48, v53, s4
	v_add3_u32 v47, v47, v52, s4
	v_add3_u32 v49, v49, v54, s4
	v_lshrrev_b32_e32 v46, 16, v46
	v_lshrrev_b32_e32 v48, 16, v48
	v_and_or_b32 v46, v47, s22, v46
	v_and_or_b32 v47, v49, s22, v48
	global_store_dwordx2 v[102:103], v[46:47], off offset:512
	global_load_dwordx4 v[46:49], v[134:135], off
	s_nop 0
	global_load_dwordx4 v[52:55], v[124:125], off offset:2048
	s_waitcnt vmcnt(0) lgkmcnt(0)
	v_pk_add_f32 v[48:49], v[48:49], 1.0 op_sel_hi:[1,0]
	v_pk_add_f32 v[46:47], v[46:47], 1.0 op_sel_hi:[1,0]
	v_pk_fma_f32 v[48:49], v[72:73], v[48:49], v[54:55]
	v_pk_fma_f32 v[46:47], v[70:71], v[46:47], v[52:53]
	v_bfe_u32 v53, v48, 16, 1
	v_bfe_u32 v51, v46, 16, 1
	v_bfe_u32 v52, v47, 16, 1
	v_bfe_u32 v54, v49, 16, 1
	v_add3_u32 v46, v46, v51, s4
	v_add3_u32 v48, v48, v53, s4
	v_add3_u32 v47, v47, v52, s4
	v_add3_u32 v49, v49, v54, s4
	v_lshrrev_b32_e32 v46, 16, v46
	v_lshrrev_b32_e32 v48, 16, v48
	v_and_or_b32 v46, v47, s22, v46
	v_and_or_b32 v47, v49, s22, v48
	global_store_dwordx2 v[102:103], v[46:47], off offset:1024
	global_load_dwordx4 v[46:49], v[128:129], off
	s_nop 0
	global_load_dwordx4 v[52:55], v[124:125], off offset:3072
	s_waitcnt vmcnt(0) lgkmcnt(0)
	v_pk_add_f32 v[48:49], v[48:49], 1.0 op_sel_hi:[1,0]
	v_pk_add_f32 v[46:47], v[46:47], 1.0 op_sel_hi:[1,0]
	v_pk_fma_f32 v[48:49], v[68:69], v[48:49], v[54:55]
	v_pk_fma_f32 v[46:47], v[66:67], v[46:47], v[52:53]
	v_bfe_u32 v53, v48, 16, 1
	v_bfe_u32 v51, v46, 16, 1
	v_bfe_u32 v52, v47, 16, 1
	v_bfe_u32 v54, v49, 16, 1
	v_add3_u32 v46, v46, v51, s4
	v_add3_u32 v48, v48, v53, s4
	v_add3_u32 v47, v47, v52, s4
	v_add3_u32 v49, v49, v54, s4
	v_lshrrev_b32_e32 v46, 16, v46
	v_lshrrev_b32_e32 v48, 16, v48
	v_and_or_b32 v46, v47, s22, v46
	v_and_or_b32 v47, v49, s22, v48
	global_store_dwordx2 v[102:103], v[46:47], off offset:1536
	global_load_dwordx4 v[46:49], v[126:127], off
	s_nop 0
	global_load_dwordx4 v[52:55], v[110:111], off
	s_waitcnt vmcnt(0) lgkmcnt(0)
	v_pk_add_f32 v[48:49], v[48:49], 1.0 op_sel_hi:[1,0]
	v_pk_add_f32 v[46:47], v[46:47], 1.0 op_sel_hi:[1,0]
	v_pk_fma_f32 v[48:49], v[64:65], v[48:49], v[54:55]
	v_pk_fma_f32 v[46:47], v[62:63], v[46:47], v[52:53]
	v_bfe_u32 v53, v48, 16, 1
	v_bfe_u32 v51, v46, 16, 1
	v_bfe_u32 v52, v47, 16, 1
	v_bfe_u32 v54, v49, 16, 1
	v_add3_u32 v46, v46, v51, s4
	v_add3_u32 v48, v48, v53, s4
	v_add3_u32 v47, v47, v52, s4
	v_add3_u32 v49, v49, v54, s4
	v_lshrrev_b32_e32 v46, 16, v46
	v_lshrrev_b32_e32 v48, 16, v48
	v_and_or_b32 v46, v47, s22, v46
	v_and_or_b32 v47, v49, s22, v48
	global_store_dwordx2 v[102:103], v[46:47], off offset:2048
	global_load_dwordx4 v[46:49], v[120:121], off
	s_nop 0
	global_load_dwordx4 v[52:55], v[110:111], off offset:1024
	s_waitcnt vmcnt(0) lgkmcnt(0)
	v_pk_add_f32 v[48:49], v[48:49], 1.0 op_sel_hi:[1,0]
	v_pk_add_f32 v[46:47], v[46:47], 1.0 op_sel_hi:[1,0]
	v_pk_fma_f32 v[48:49], v[60:61], v[48:49], v[54:55]
	v_pk_fma_f32 v[46:47], v[58:59], v[46:47], v[52:53]
	v_bfe_u32 v53, v48, 16, 1
	v_bfe_u32 v51, v46, 16, 1
	v_bfe_u32 v52, v47, 16, 1
	v_bfe_u32 v54, v49, 16, 1
	v_add3_u32 v46, v46, v51, s4
	v_add3_u32 v48, v48, v53, s4
	v_add3_u32 v47, v47, v52, s4
	v_add3_u32 v49, v49, v54, s4
	v_lshrrev_b32_e32 v46, 16, v46
	v_lshrrev_b32_e32 v48, 16, v48
	v_and_or_b32 v46, v47, s22, v46
	v_and_or_b32 v47, v49, s22, v48
	global_store_dwordx2 v[102:103], v[46:47], off offset:2560
	global_load_dwordx4 v[46:49], v[116:117], off
	s_nop 0
	global_load_dwordx4 v[52:55], v[110:111], off offset:2048
	v_pk_add_f32 v[58:59], v[150:151], v[150:151] op_sel:[0,1] op_sel_hi:[1,0]
	v_pk_add_f32 v[60:61], v[144:145], v[146:147]
	v_mov_b32_e32 v59, v198
	s_waitcnt vmcnt(0) lgkmcnt(0)
	v_pk_add_f32 v[48:49], v[48:49], 1.0 op_sel_hi:[1,0]
	v_pk_add_f32 v[46:47], v[46:47], 1.0 op_sel_hi:[1,0]
	v_pk_fma_f32 v[48:49], v[56:57], v[48:49], v[54:55]
	v_pk_fma_f32 v[46:47], v[82:83], v[46:47], v[52:53]
	v_bfe_u32 v53, v48, 16, 1
	v_bfe_u32 v51, v46, 16, 1
	v_bfe_u32 v52, v47, 16, 1
	v_bfe_u32 v54, v49, 16, 1
	v_add3_u32 v46, v46, v51, s4
	v_add3_u32 v48, v48, v53, s4
	v_add3_u32 v47, v47, v52, s4
	v_add3_u32 v49, v49, v54, s4
	v_lshrrev_b32_e32 v46, 16, v46
	v_lshrrev_b32_e32 v48, 16, v48
	v_and_or_b32 v46, v47, s22, v46
	v_and_or_b32 v47, v49, s22, v48
	global_store_dwordx2 v[102:103], v[46:47], off offset:3072
	global_load_dwordx4 v[46:49], v[112:113], off
	s_nop 0
	global_load_dwordx4 v[52:55], v[110:111], off offset:3072
	v_pk_add_f32 v[56:57], v[148:149], v[148:149] op_sel:[0,1] op_sel_hi:[1,0]
	s_waitcnt vmcnt(0) lgkmcnt(0)
	v_pk_add_f32 v[48:49], v[48:49], 1.0 op_sel_hi:[1,0]
	v_pk_add_f32 v[46:47], v[46:47], 1.0 op_sel_hi:[1,0]
	v_pk_fma_f32 v[48:49], v[86:87], v[48:49], v[54:55]
	v_pk_fma_f32 v[46:47], v[84:85], v[46:47], v[52:53]
	v_bfe_u32 v53, v48, 16, 1
	v_bfe_u32 v51, v46, 16, 1
	v_bfe_u32 v52, v47, 16, 1
	v_bfe_u32 v54, v49, 16, 1
	v_add3_u32 v46, v46, v51, s4
	v_add3_u32 v48, v48, v53, s4
	v_add3_u32 v47, v47, v52, s4
	v_add3_u32 v49, v49, v54, s4
	v_lshrrev_b32_e32 v46, 16, v46
	v_lshrrev_b32_e32 v48, 16, v48
	v_and_or_b32 v46, v47, s22, v46
	v_and_or_b32 v47, v49, s22, v48
	global_store_dwordx2 v[102:103], v[46:47], off offset:3584
	global_load_dwordx4 v[46:49], v[142:143], off
	s_nop 0
	global_load_dwordx4 v[52:55], v[108:109], off
	v_mov_b32_e32 v57, v197
	s_waitcnt vmcnt(0) lgkmcnt(0)
	v_pk_add_f32 v[48:49], v[48:49], 1.0 op_sel_hi:[1,0]
	v_pk_add_f32 v[46:47], v[46:47], 1.0 op_sel_hi:[1,0]
	v_pk_fma_f32 v[48:49], v[158:159], v[48:49], v[54:55]
	v_pk_fma_f32 v[46:47], v[88:89], v[46:47], v[52:53]
	v_bfe_u32 v53, v48, 16, 1
	v_bfe_u32 v51, v46, 16, 1
	v_bfe_u32 v52, v47, 16, 1
	v_bfe_u32 v54, v49, 16, 1
	v_add3_u32 v46, v46, v51, s4
	v_add3_u32 v48, v48, v53, s4
	v_add3_u32 v47, v47, v52, s4
	v_add3_u32 v49, v49, v54, s4
	v_lshrrev_b32_e32 v46, 16, v46
	v_lshrrev_b32_e32 v48, 16, v48
	v_and_or_b32 v46, v47, s22, v46
	v_and_or_b32 v47, v49, s22, v48
	global_store_dwordx2 v[104:105], v[46:47], off
	global_load_dwordx4 v[46:49], v[140:141], off
	s_nop 0
	global_load_dwordx4 v[52:55], v[108:109], off offset:1024
	v_pk_mul_f32 v[44:45], v[44:45], v[50:51] op_sel_hi:[1,0]
	v_pk_mul_f32 v[42:43], v[42:43], v[50:51] op_sel_hi:[1,0]
	v_pk_mul_f32 v[44:45], v[44:45], v[8:9]
	v_pk_mul_f32 v[42:43], v[42:43], v[6:7]
	s_waitcnt vmcnt(0) lgkmcnt(0)
	v_pk_add_f32 v[48:49], v[48:49], 1.0 op_sel_hi:[1,0]
	v_pk_add_f32 v[46:47], v[46:47], 1.0 op_sel_hi:[1,0]
	v_pk_fma_f32 v[44:45], v[44:45], v[48:49], v[54:55]
	v_pk_fma_f32 v[42:43], v[42:43], v[46:47], v[52:53]
	v_bfe_u32 v48, v44, 16, 1
	v_bfe_u32 v46, v42, 16, 1
	v_bfe_u32 v47, v43, 16, 1
	v_bfe_u32 v49, v45, 16, 1
	v_add3_u32 v42, v42, v46, s4
	v_add3_u32 v44, v44, v48, s4
	v_add3_u32 v43, v43, v47, s4
	v_add3_u32 v45, v45, v49, s4
	v_lshrrev_b32_e32 v42, 16, v42
	v_lshrrev_b32_e32 v44, 16, v44
	v_and_or_b32 v42, v43, s22, v42
	v_and_or_b32 v43, v45, s22, v44
	global_store_dwordx2 v[104:105], v[42:43], off offset:512
	global_load_dwordx4 v[42:45], v[136:137], off
	s_nop 0
	global_load_dwordx4 v[46:49], v[108:109], off offset:2048
	v_pk_add_f32 v[52:53], v[56:57], v[58:59]
	s_waitcnt vmcnt(0) lgkmcnt(0)
	v_pk_add_f32 v[44:45], v[44:45], 1.0 op_sel_hi:[1,0]
	v_pk_add_f32 v[52:53], v[52:53], v[60:61]
	v_pk_add_f32 v[42:43], v[42:43], 1.0 op_sel_hi:[1,0]
	v_add_f32_e32 v51, v52, v53
	ds_bpermute_b32 v52, v1, v51
	s_waitcnt lgkmcnt(0)
	v_add_f32_e32 v51, v51, v52
	ds_bpermute_b32 v52, v131, v51
	s_waitcnt lgkmcnt(0)
	v_add_f32_e32 v51, v51, v52
	v_pk_mul_f32 v[40:41], v[40:41], v[50:51] op_sel_hi:[1,0]
	v_pk_mul_f32 v[38:39], v[38:39], v[50:51] op_sel_hi:[1,0]
	v_pk_mul_f32 v[40:41], v[40:41], v[12:13]
	v_pk_mul_f32 v[38:39], v[38:39], v[10:11]
	v_pk_fma_f32 v[40:41], v[40:41], v[44:45], v[48:49]
	v_pk_fma_f32 v[38:39], v[38:39], v[42:43], v[46:47]
	v_bfe_u32 v44, v40, 16, 1
	v_bfe_u32 v42, v38, 16, 1
	v_bfe_u32 v43, v39, 16, 1
	v_bfe_u32 v45, v41, 16, 1
	v_add3_u32 v38, v38, v42, s4
	v_add3_u32 v40, v40, v44, s4
	v_add3_u32 v39, v39, v43, s4
	v_add3_u32 v41, v41, v45, s4
	v_lshrrev_b32_e32 v38, 16, v38
	v_lshrrev_b32_e32 v40, 16, v40
	v_and_or_b32 v38, v39, s22, v38
	v_and_or_b32 v39, v41, s22, v40
	global_store_dwordx2 v[104:105], v[38:39], off offset:1024
	global_load_dwordx4 v[38:41], v[122:123], off
	s_nop 0
	global_load_dwordx4 v[42:45], v[108:109], off offset:3072
	v_pk_mul_f32 v[36:37], v[36:37], v[50:51] op_sel_hi:[1,0]
	v_pk_mul_f32 v[34:35], v[34:35], v[50:51] op_sel_hi:[1,0]
	v_pk_mul_f32 v[36:37], v[36:37], v[16:17]
	v_pk_mul_f32 v[34:35], v[34:35], v[14:15]
	ds_bpermute_b32 v46, v133, v51
	s_waitcnt lgkmcnt(0)
	v_add_f32_e32 v46, v51, v46
	ds_bpermute_b32 v47, v152, v46
	s_waitcnt lgkmcnt(0)
	v_add_f32_e32 v46, v46, v47
	ds_bpermute_b32 v47, v153, v46
	s_waitcnt lgkmcnt(0)
	v_add_f32_e32 v46, v46, v47
	ds_bpermute_b32 v47, v154, v46
	s_waitcnt lgkmcnt(0)
	v_add_f32_e32 v46, v46, v47
	v_fmamk_f32 v46, v46, 0x3a800000, v155
	v_mul_f32_e32 v47, 0x4f800000, v46
	v_cmp_gt_f32_e32 vcc, s3, v46
	s_waitcnt vmcnt(0)
	v_pk_add_f32 v[40:41], v[40:41], 1.0 op_sel_hi:[1,0]
	v_pk_add_f32 v[38:39], v[38:39], 1.0 op_sel_hi:[1,0]
	v_pk_fma_f32 v[36:37], v[36:37], v[40:41], v[44:45]
	v_pk_fma_f32 v[34:35], v[34:35], v[38:39], v[42:43]
	v_bfe_u32 v40, v36, 16, 1
	v_bfe_u32 v38, v34, 16, 1
	v_bfe_u32 v39, v35, 16, 1
	v_bfe_u32 v41, v37, 16, 1
	v_add3_u32 v34, v34, v38, s4
	v_add3_u32 v36, v36, v40, s4
	v_add3_u32 v35, v35, v39, s4
	v_add3_u32 v37, v37, v41, s4
	v_lshrrev_b32_e32 v34, 16, v34
	v_lshrrev_b32_e32 v36, 16, v36
	v_and_or_b32 v34, v35, s22, v34
	v_and_or_b32 v35, v37, s22, v36
	global_store_dwordx2 v[104:105], v[34:35], off offset:1536
	global_load_dwordx4 v[34:37], v[118:119], off
	s_nop 0
	global_load_dwordx4 v[38:41], v[106:107], off
	v_cndmask_b32_e32 v42, v46, v47, vcc
	v_sqrt_f32_e32 v43, v42
	s_waitcnt vmcnt(0) lgkmcnt(0)
	v_pk_add_f32 v[36:37], v[36:37], 1.0 op_sel_hi:[1,0]
	v_add_u32_e32 v44, -1, v43
	v_add_u32_e32 v45, 1, v43
	v_fma_f32 v46, -v44, v43, v42
	v_fma_f32 v47, -v45, v43, v42
	v_cmp_ge_f32_e64 s[6:7], 0, v46
	v_pk_add_f32 v[34:35], v[34:35], 1.0 op_sel_hi:[1,0]
	s_nop 0
	v_cndmask_b32_e64 v43, v43, v44, s[6:7]
	v_cmp_lt_f32_e64 s[6:7], 0, v47
	s_nop 1
	v_cndmask_b32_e64 v43, v43, v45, s[6:7]
	v_mul_f32_e32 v44, 0x37800000, v43
	v_cndmask_b32_e32 v43, v43, v44, vcc
	v_cmp_class_f32_e32 vcc, v42, v156
	s_nop 1
	v_cndmask_b32_e32 v42, v43, v42, vcc
	v_div_scale_f32 v43, s[6:7], v42, v42, 1.0
	v_rcp_f32_e32 v45, v43
	v_div_scale_f32 v44, vcc, 1.0, v42, 1.0
	v_fma_f32 v46, -v43, v45, 1.0
	v_fmac_f32_e32 v45, v46, v45
	v_mul_f32_e32 v46, v44, v45
	v_fma_f32 v47, -v43, v46, v44
	v_fmac_f32_e32 v46, v47, v45
	v_fma_f32 v43, -v43, v46, v44
	v_div_fmas_f32 v43, v43, v45, v46
	v_div_fixup_f32 v42, v43, v42, 1.0
	v_pk_mul_f32 v[32:33], v[32:33], v[42:43] op_sel_hi:[1,0]
	v_pk_mul_f32 v[30:31], v[30:31], v[42:43] op_sel_hi:[1,0]
	v_pk_mul_f32 v[32:33], v[32:33], v[4:5]
	v_pk_mul_f32 v[30:31], v[30:31], v[2:3]
	v_pk_fma_f32 v[32:33], v[32:33], v[36:37], v[40:41]
	v_pk_fma_f32 v[30:31], v[30:31], v[34:35], v[38:39]
	v_bfe_u32 v36, v32, 16, 1
	v_bfe_u32 v34, v30, 16, 1
	v_bfe_u32 v35, v31, 16, 1
	v_bfe_u32 v37, v33, 16, 1
	v_add3_u32 v30, v30, v34, s4
	v_add3_u32 v32, v32, v36, s4
	v_add3_u32 v31, v31, v35, s4
	v_add3_u32 v33, v33, v37, s4
	v_lshrrev_b32_e32 v30, 16, v30
	v_lshrrev_b32_e32 v32, 16, v32
	v_and_or_b32 v30, v31, s22, v30
	v_and_or_b32 v31, v33, s22, v32
	global_store_dwordx2 v[104:105], v[30:31], off offset:2048
	global_load_dwordx4 v[30:33], v[114:115], off
	s_nop 0
	global_load_dwordx4 v[34:37], v[106:107], off offset:1024
	v_pk_mul_f32 v[28:29], v[28:29], v[42:43] op_sel_hi:[1,0]
	v_pk_mul_f32 v[26:27], v[26:27], v[42:43] op_sel_hi:[1,0]
	v_pk_mul_f32 v[28:29], v[28:29], v[8:9]
	v_pk_mul_f32 v[26:27], v[26:27], v[6:7]
	v_lshl_add_u64 v[38:39], s[20:21], 0, v[98:99]
	v_pk_mul_f32 v[24:25], v[24:25], v[42:43] op_sel_hi:[1,0]
	v_pk_mul_f32 v[22:23], v[22:23], v[42:43] op_sel_hi:[1,0]
	v_pk_mul_f32 v[24:25], v[24:25], v[12:13]
	v_pk_mul_f32 v[22:23], v[22:23], v[10:11]
	v_pk_mul_f32 v[20:21], v[20:21], v[42:43] op_sel_hi:[1,0]
	v_pk_mul_f32 v[18:19], v[18:19], v[42:43] op_sel_hi:[1,0]
	v_pk_mul_f32 v[20:21], v[20:21], v[16:17]
	v_pk_mul_f32 v[18:19], v[18:19], v[14:15]
	s_waitcnt vmcnt(0) lgkmcnt(0)
	v_pk_add_f32 v[32:33], v[32:33], 1.0 op_sel_hi:[1,0]
	v_pk_add_f32 v[30:31], v[30:31], 1.0 op_sel_hi:[1,0]
	v_pk_fma_f32 v[28:29], v[28:29], v[32:33], v[36:37]
	v_pk_fma_f32 v[26:27], v[26:27], v[30:31], v[34:35]
	v_bfe_u32 v32, v28, 16, 1
	v_bfe_u32 v30, v26, 16, 1
	v_bfe_u32 v31, v27, 16, 1
	v_bfe_u32 v33, v29, 16, 1
	v_add3_u32 v26, v26, v30, s4
	v_add3_u32 v28, v28, v32, s4
	v_add3_u32 v27, v27, v31, s4
	v_add3_u32 v29, v29, v33, s4
	v_lshrrev_b32_e32 v26, 16, v26
	v_lshrrev_b32_e32 v28, 16, v28
	v_and_or_b32 v26, v27, s22, v26
	v_and_or_b32 v27, v29, s22, v28
	global_store_dwordx2 v[104:105], v[26:27], off offset:2560
	global_load_dwordx4 v[26:29], v[38:39], off
	s_nop 0
	global_load_dwordx4 v[30:33], v[106:107], off offset:2048
	v_lshl_add_u64 v[34:35], s[20:21], 0, v[100:101]
	s_waitcnt vmcnt(0) lgkmcnt(0)
	v_pk_add_f32 v[28:29], v[28:29], 1.0 op_sel_hi:[1,0]
	v_pk_add_f32 v[26:27], v[26:27], 1.0 op_sel_hi:[1,0]
	v_pk_fma_f32 v[24:25], v[24:25], v[28:29], v[32:33]
	v_pk_fma_f32 v[22:23], v[22:23], v[26:27], v[30:31]
	v_bfe_u32 v28, v24, 16, 1
	v_bfe_u32 v26, v22, 16, 1
	v_bfe_u32 v27, v23, 16, 1
	v_bfe_u32 v29, v25, 16, 1
	v_add3_u32 v22, v22, v26, s4
	v_add3_u32 v24, v24, v28, s4
	v_add3_u32 v23, v23, v27, s4
	v_add3_u32 v25, v25, v29, s4
	v_lshrrev_b32_e32 v22, 16, v22
	v_lshrrev_b32_e32 v24, 16, v24
	v_and_or_b32 v22, v23, s22, v22
	v_and_or_b32 v23, v25, s22, v24
	global_store_dwordx2 v[104:105], v[22:23], off offset:3072
	global_load_dwordx4 v[22:25], v[34:35], off
	s_nop 0
	global_load_dwordx4 v[26:29], v[106:107], off offset:3072
	s_waitcnt vmcnt(0) lgkmcnt(0)
	v_pk_add_f32 v[24:25], v[24:25], 1.0 op_sel_hi:[1,0]
	v_pk_add_f32 v[22:23], v[22:23], 1.0 op_sel_hi:[1,0]
	v_pk_fma_f32 v[20:21], v[20:21], v[24:25], v[28:29]
	v_pk_fma_f32 v[18:19], v[18:19], v[22:23], v[26:27]
	v_bfe_u32 v24, v20, 16, 1
	v_bfe_u32 v22, v18, 16, 1
	v_bfe_u32 v23, v19, 16, 1
	v_bfe_u32 v25, v21, 16, 1
	v_add3_u32 v18, v18, v22, s4
	v_add3_u32 v20, v20, v24, s4
	v_add3_u32 v19, v19, v23, s4
	v_add3_u32 v21, v21, v25, s4
	v_lshrrev_b32_e32 v18, 16, v18
	v_lshrrev_b32_e32 v20, 16, v20
	v_and_or_b32 v18, v19, s22, v18
	v_and_or_b32 v19, v21, s22, v20
	global_store_dwordx2 v[104:105], v[18:19], off offset:3584
	s_cbranch_scc1 .LBB0_3611

.LBB0_3682:
	s_and_b64 vcc, exec, s[6:7]
	s_cbranch_vccz .LBB0_4134
	s_lshl_b32 s14, s14, 8
	v_add_u32_e32 v138, s14, v133
	v_mov_b64_e32 v[146:147], s[22:23]
	v_mad_i64_i32 v[148:149], s[6:7], v138, s80, v[146:147]
	s_lshl_b32 s10, s10, 8
	s_lshl_b64 s[6:7], s[10:11], 2
	v_lshl_add_u64 v[148:149], v[148:149], 0, s[6:7]
	v_mov_b32_e32 v145, v139
	v_lshl_add_u64 v[148:149], v[148:149], 0, v[144:145]
	global_store_dwordx4 v[148:149], v[126:129], off
	global_store_dwordx4 v[148:149], v[122:125], off offset:64
	global_store_dwordx4 v[148:149], v[106:109], off offset:512
	global_store_dwordx4 v[148:149], v[98:101], off offset:576
	s_nop 1
	v_add_u32_e32 v98, s14, v170
	v_mad_i64_i32 v[98:99], s[8:9], v98, s80, v[146:147]
	v_lshl_add_u64 v[98:99], v[98:99], 0, s[6:7]
	v_lshl_add_u64 v[98:99], v[98:99], 0, v[144:145]
	global_store_dwordx4 v[98:99], v[118:121], off
	global_store_dwordx4 v[98:99], v[114:117], off offset:64
	global_store_dwordx4 v[98:99], v[90:93], off offset:512
	global_store_dwordx4 v[98:99], v[82:85], off offset:576
	s_nop 1
	v_add_u32_e32 v82, s14, v171
	v_mad_i64_i32 v[82:83], s[8:9], v82, s80, v[146:147]
	v_lshl_add_u64 v[82:83], v[82:83], 0, s[6:7]
	v_lshl_add_u64 v[82:83], v[82:83], 0, v[144:145]
	global_store_dwordx4 v[82:83], v[110:113], off
	global_store_dwordx4 v[82:83], v[102:105], off offset:64
	global_store_dwordx4 v[82:83], v[78:81], off offset:512
	global_store_dwordx4 v[82:83], v[74:77], off offset:576
	s_nop 1
	v_add_u32_e32 v74, s14, v172
	v_mad_i64_i32 v[74:75], s[8:9], v74, s80, v[146:147]
	v_lshl_add_u64 v[74:75], v[74:75], 0, s[6:7]
	v_lshl_add_u64 v[74:75], v[74:75], 0, v[144:145]
	global_store_dwordx4 v[74:75], v[94:97], off
	global_store_dwordx4 v[74:75], v[86:89], off offset:64
	global_store_dwordx4 v[74:75], v[70:73], off offset:512
	global_store_dwordx4 v[74:75], v[66:69], off offset:576
	s_nop 1
	v_add_u32_e32 v66, 0x80, v138
	v_mad_i64_i32 v[66:67], s[8:9], v66, s80, v[146:147]
	v_lshl_add_u64 v[66:67], v[66:67], 0, s[6:7]
	v_lshl_add_u64 v[66:67], v[66:67], 0, v[144:145]
	global_store_dwordx4 v[66:67], v[62:65], off
	global_store_dwordx4 v[66:67], v[58:61], off offset:64
	global_store_dwordx4 v[66:67], v[42:45], off offset:512
	global_store_dwordx4 v[66:67], v[34:37], off offset:576
	s_nop 1
	v_add_u32_e32 v34, 0x90, v138
	v_mad_i64_i32 v[34:35], s[8:9], v34, s80, v[146:147]
	v_lshl_add_u64 v[34:35], v[34:35], 0, s[6:7]
	v_lshl_add_u64 v[34:35], v[34:35], 0, v[144:145]
	global_store_dwordx4 v[34:35], v[54:57], off
	global_store_dwordx4 v[34:35], v[50:53], off offset:64
	global_store_dwordx4 v[34:35], v[26:29], off offset:512
	global_store_dwordx4 v[34:35], v[18:21], off offset:576
	s_nop 1
	v_add_u32_e32 v18, 0xa0, v138
	v_mad_i64_i32 v[18:19], s[8:9], v18, s80, v[146:147]
	v_lshl_add_u64 v[18:19], v[18:19], 0, s[6:7]
	v_lshl_add_u64 v[18:19], v[18:19], 0, v[144:145]
	global_store_dwordx4 v[18:19], v[46:49], off
	global_store_dwordx4 v[18:19], v[38:41], off offset:64
	global_store_dwordx4 v[18:19], v[14:17], off offset:512
	global_store_dwordx4 v[18:19], v[10:13], off offset:576
	s_nop 1
	v_add_u32_e32 v10, 0xb0, v138
	v_mad_i64_i32 v[10:11], s[8:9], v10, s80, v[146:147]
	v_lshl_add_u64 v[10:11], v[10:11], 0, s[6:7]
	v_lshl_add_u64 v[10:11], v[10:11], 0, v[144:145]
	global_store_dwordx4 v[10:11], v[30:33], off
	global_store_dwordx4 v[10:11], v[22:25], off offset:64
	global_store_dwordx4 v[10:11], v[6:9], off offset:512
	global_store_dwordx4 v[10:11], v[2:5], off offset:576
	s_mov_b64 s[6:7], -1
	s_and_b64 vcc, exec, s[62:63]
	s_cbranch_vccz .LBB0_3675
	s_branch .LBB0_4135

.LBB0_3685:
	v_mov_b32_e32 v138, v1
	v_mov_b32_e32 v145, v131
	s_lshl_b32 s6, s14, 8
	s_add_i32 s6, s6, s57
	v_add_u32_e32 v154, s6, v138
	v_lshlrev_b32_e32 v138, 6, v138
	v_lshl_add_u32 v146, v145, 2, s70
	v_and_b32_e32 v145, 0x3c0, v138
	v_ashrrev_i32_e32 v138, 10, v154
	v_ashrrev_i32_e32 v155, 31, v154
	v_and_b32_e32 v168, -2, v138
	v_lshrrev_b32_e32 v138, 3, v154
	v_lshlrev_b64 v[158:159], 9, v[154:155]
	v_lshlrev_b64 v[156:157], 10, v[154:155]
	v_and_b32_e32 v155, 0xfe, v138
	v_and_b32_e32 v138, 0x1fff, v154
	s_cmp_gt_i32 s10, 1
	v_cmp_lt_u32_e64 s[8:9], s77, v138
	v_add_u32_e32 v138, 0xffffe200, v138
	s_cselect_b64 s[68:69], -1, 0
	s_cmp_lt_i32 s10, 2
	v_ashrrev_i32_e32 v160, 13, v154
	v_lshlrev_b64 v[162:163], 10, v[138:139]
	s_mov_b64 s[6:7], -1
	s_cbranch_scc1 .LBB0_3697
	v_bfe_u32 v138, v126, 16, 1
	v_add3_u32 v138, v126, v138, s78
	v_bfe_u32 v147, v127, 16, 1
	v_lshrrev_b32_e32 v138, 16, v138
	v_add3_u32 v147, v127, v147, s78
	v_and_or_b32 v148, v147, s79, v138
	v_bfe_u32 v138, v128, 16, 1
	v_add3_u32 v138, v128, v138, s78
	v_bfe_u32 v147, v129, 16, 1
	v_lshrrev_b32_e32 v138, 16, v138
	v_add3_u32 v147, v129, v147, s78
	v_and_or_b32 v149, v147, s79, v138
	s_cmp_lt_i32 s10, 3
	s_cbranch_scc1 .LBB0_3694
	s_cmp_lg_u32 s10, 3
	s_cbranch_scc0 .LBB0_3691
	v_lshlrev_b32_e32 v152, 1, v146
	v_lshl_add_u64 v[150:151], s[50:51], 0, v[158:159]
	v_ashrrev_i32_e32 v153, 31, v152
	v_lshl_add_u64 v[150:151], v[150:151], 0, v[152:153]
	global_store_dwordx2 v[150:151], v[148:149], off
	s_and_saveexec_b64 s[6:7], s[8:9]
	s_cbranch_execz .LBB0_3690
	v_ashrrev_i32_e32 v161, 31, v160
	v_lshlrev_b64 v[150:151], 19, v[160:161]
	v_lshl_add_u64 v[150:151], s[52:53], 0, v[150:151]
	v_lshl_add_u64 v[150:151], v[150:151], 0, v[162:163]
	v_ashrrev_i32_e32 v147, 31, v146
	v_lshl_add_u64 v[150:151], v[146:147], 2, v[150:151]
	v_add_co_u32_e32 v150, vcc, 0x100000, v150
	s_nop 1
	v_addc_co_u32_e32 v151, vcc, 0, v151, vcc
	global_store_dwordx4 v[150:151], v[126:129], off

.LBB0_3697:
	s_lshl_b32 s26, s10, 8
	v_add_u32_e32 v148, s26, v146
	s_and_b64 vcc, exec, s[6:7]
	v_lshl_add_u64 v[164:165], s[54:55], 0, v[156:157]
	v_ashrrev_i32_e32 v149, 31, v148
	s_cbranch_vccz .LBB0_3699
	v_pk_mul_f32 v[152:153], v[126:127], s[56:57] op_sel_hi:[1,0]
	v_pk_mul_f32 v[150:151], v[128:129], s[56:57] op_sel_hi:[1,0]
	v_bfe_u32 v138, v152, 16, 1
	v_add3_u32 v138, v152, v138, s78
	v_bfe_u32 v147, v153, 16, 1
	v_lshrrev_b32_e32 v138, 16, v138
	v_add3_u32 v147, v153, v147, s78
	v_and_or_b32 v152, v147, s79, v138
	v_bfe_u32 v138, v150, 16, 1
	v_add3_u32 v138, v150, v138, s78
	v_bfe_u32 v147, v151, 16, 1
	v_lshrrev_b32_e32 v138, 16, v138
	v_add3_u32 v147, v151, v147, s78
	v_and_or_b32 v153, v147, s79, v138
	v_lshl_add_u64 v[150:151], v[148:149], 1, v[164:165]
	global_store_dwordx2 v[150:151], v[152:153], off
.LBB0_3699:
	v_cndmask_b32_e64 v138, 0, 1, s[68:69]
	v_add_u32_e32 v178, 16, v146
	v_cmp_ne_u32_e64 s[6:7], 1, v138
	s_andn2_b64 vcc, exec, s[68:69]
	s_mov_b64 s[68:69], -1
	s_cbranch_vccnz .LBB0_3735
	v_bfe_u32 v138, v122, 16, 1
	v_add3_u32 v138, v122, v138, s78
	v_bfe_u32 v147, v123, 16, 1
	v_lshrrev_b32_e32 v138, 16, v138
	v_add3_u32 v147, v123, v147, s78
	v_and_or_b32 v150, v147, s79, v138
	v_bfe_u32 v138, v124, 16, 1
	v_add3_u32 v138, v124, v138, s78
	v_bfe_u32 v147, v125, 16, 1
	v_lshrrev_b32_e32 v138, 16, v138
	v_add3_u32 v147, v125, v147, s78
	v_and_or_b32 v151, v147, s79, v138
	s_cmp_lt_i32 s10, 3
	s_cbranch_scc1 .LBB0_3708
	s_cmp_lg_u32 s10, 3
	s_cbranch_scc0 .LBB0_3705
	v_lshlrev_b32_e32 v166, 1, v178
	v_lshl_add_u64 v[152:153], s[50:51], 0, v[158:159]
	v_ashrrev_i32_e32 v167, 31, v166
	v_lshl_add_u64 v[152:153], v[152:153], 0, v[166:167]
	global_store_dwordx2 v[152:153], v[150:151], off
	s_and_saveexec_b64 s[68:69], s[8:9]
	s_cbranch_execz .LBB0_3704
	v_ashrrev_i32_e32 v161, 31, v160
	v_lshlrev_b64 v[152:153], 19, v[160:161]
	v_lshl_add_u64 v[152:153], s[52:53], 0, v[152:153]
	v_lshl_add_u64 v[152:153], v[152:153], 0, v[162:163]
	v_ashrrev_i32_e32 v147, 31, v146
	v_lshl_add_u64 v[152:153], v[146:147], 2, v[152:153]
	v_add_co_u32_e32 v152, vcc, 0x100000, v152
	s_nop 1
	v_addc_co_u32_e32 v153, vcc, 0, v153, vcc
	global_store_dwordx4 v[152:153], v[122:125], off offset:64

.LBB0_3712:
	v_bfe_u32 v138, v106, 16, 1
	v_add3_u32 v138, v106, v138, s78
	v_bfe_u32 v147, v107, 16, 1
	v_lshrrev_b32_e32 v138, 16, v138
	v_add3_u32 v147, v107, v147, s78
	v_and_or_b32 v152, v147, s79, v138
	v_bfe_u32 v138, v108, 16, 1
	v_add3_u32 v138, v108, v138, s78
	v_bfe_u32 v147, v109, 16, 1
	v_lshrrev_b32_e32 v138, 16, v138
	v_add3_u32 v147, v109, v147, s78
	v_and_or_b32 v153, v147, s79, v138
	s_cmp_lt_i32 s10, 3
	s_cbranch_scc1 .LBB0_3720
	s_cmp_lg_u32 s10, 3
	s_cbranch_scc0 .LBB0_3717
	v_lshlrev_b32_e32 v182, 1, v180
	v_lshl_add_u64 v[166:167], s[50:51], 0, v[158:159]
	v_ashrrev_i32_e32 v183, 31, v182
	v_lshl_add_u64 v[166:167], v[166:167], 0, v[182:183]
	global_store_dwordx2 v[166:167], v[152:153], off
	s_and_saveexec_b64 s[68:69], s[8:9]
	s_cbranch_execz .LBB0_3716
	v_ashrrev_i32_e32 v161, 31, v160
	v_lshlrev_b64 v[166:167], 19, v[160:161]
	v_lshl_add_u64 v[166:167], s[52:53], 0, v[166:167]
	v_lshl_add_u64 v[166:167], v[166:167], 0, v[162:163]
	v_ashrrev_i32_e32 v147, 31, v146
	v_lshl_add_u64 v[166:167], v[146:147], 2, v[166:167]
	v_add_co_u32_e32 v166, vcc, 0x100000, v166
	s_nop 1
	v_addc_co_u32_e32 v167, vcc, 0, v167, vcc
	global_store_dwordx4 v[166:167], v[106:109], off offset:512

.LBB0_3724:
	v_bfe_u32 v138, v98, 16, 1
	v_add3_u32 v138, v98, v138, s78
	v_bfe_u32 v147, v99, 16, 1
	v_lshrrev_b32_e32 v138, 16, v138
	v_add3_u32 v147, v99, v147, s78
	v_and_or_b32 v166, v147, s79, v138
	v_bfe_u32 v138, v100, 16, 1
	v_add3_u32 v138, v100, v138, s78
	v_bfe_u32 v147, v101, 16, 1
	v_lshrrev_b32_e32 v138, 16, v138
	v_add3_u32 v147, v101, v147, s78
	v_and_or_b32 v167, v147, s79, v138
	s_cmp_lt_i32 s10, 3
	s_cbranch_scc1 .LBB0_3732
	s_cmp_lg_u32 s10, 3
	s_cbranch_scc0 .LBB0_3729
	v_lshlrev_b32_e32 v184, 1, v179
	v_lshl_add_u64 v[182:183], s[50:51], 0, v[158:159]
	v_ashrrev_i32_e32 v185, 31, v184
	v_lshl_add_u64 v[182:183], v[182:183], 0, v[184:185]
	global_store_dwordx2 v[182:183], v[166:167], off
	s_and_saveexec_b64 s[68:69], s[8:9]
	s_cbranch_execz .LBB0_3728
	v_ashrrev_i32_e32 v161, 31, v160
	v_lshlrev_b64 v[160:161], 19, v[160:161]
	v_lshl_add_u64 v[160:161], s[52:53], 0, v[160:161]
	v_lshl_add_u64 v[160:161], v[160:161], 0, v[162:163]
	v_ashrrev_i32_e32 v147, 31, v146
	v_lshl_add_u64 v[160:161], v[146:147], 2, v[160:161]
	v_add_co_u32_e32 v160, vcc, 0x100000, v160
	s_nop 1
	v_addc_co_u32_e32 v161, vcc, 0, v161, vcc
	global_store_dwordx4 v[160:161], v[98:101], off offset:576

.LBB0_3735:
	v_add_u32_e32 v150, s26, v178
	s_and_b64 vcc, exec, s[68:69]
	v_ashrrev_i32_e32 v151, 31, v150
	s_cbranch_vccz .LBB0_3711
	v_pk_mul_f32 v[166:167], v[122:123], s[56:57] op_sel_hi:[1,0]
	v_pk_mul_f32 v[152:153], v[124:125], s[56:57] op_sel_hi:[1,0]
	v_bfe_u32 v138, v166, 16, 1
	v_add3_u32 v138, v166, v138, s78
	v_bfe_u32 v147, v167, 16, 1
	v_lshrrev_b32_e32 v138, 16, v138
	v_add3_u32 v147, v167, v147, s78
	v_and_or_b32 v166, v147, s79, v138
	v_bfe_u32 v138, v152, 16, 1
	v_add3_u32 v138, v152, v138, s78
	v_bfe_u32 v147, v153, 16, 1
	v_lshrrev_b32_e32 v138, 16, v138
	v_add3_u32 v147, v153, v147, s78
	v_and_or_b32 v167, v147, s79, v138
	v_lshl_add_u64 v[152:153], v[150:151], 1, v[164:165]
	global_store_dwordx2 v[152:153], v[166:167], off
	v_add_u32_e32 v180, 0x80, v146
	s_and_b64 vcc, exec, s[6:7]
	s_mov_b64 s[68:69], -1
	s_cbranch_vccz .LBB0_3712
.LBB0_3737:
	v_add_u32_e32 v152, s26, v180
	s_and_b64 vcc, exec, s[68:69]
	v_ashrrev_i32_e32 v153, 31, v152
	s_cbranch_vccz .LBB0_3723
	v_pk_mul_f32 v[182:183], v[106:107], s[56:57] op_sel_hi:[1,0]
	v_pk_mul_f32 v[166:167], v[108:109], s[56:57] op_sel_hi:[1,0]
	v_bfe_u32 v138, v182, 16, 1
	v_add3_u32 v138, v182, v138, s78
	v_bfe_u32 v147, v183, 16, 1
	v_lshrrev_b32_e32 v138, 16, v138
	v_add3_u32 v147, v183, v147, s78
	v_and_or_b32 v182, v147, s79, v138
	v_bfe_u32 v138, v166, 16, 1
	v_add3_u32 v138, v166, v138, s78
	v_bfe_u32 v147, v167, 16, 1
	v_lshrrev_b32_e32 v138, 16, v138
	v_add3_u32 v147, v167, v147, s78
	v_and_or_b32 v183, v147, s79, v138
	v_lshl_add_u64 v[166:167], v[152:153], 1, v[164:165]
	global_store_dwordx2 v[166:167], v[182:183], off
	v_add_u32_e32 v179, 0x90, v146
	s_and_b64 vcc, exec, s[6:7]
	s_mov_b64 s[68:69], -1
	s_cbranch_vccz .LBB0_3724
.LBB0_3739:
	v_add_u32_e32 v156, s26, v179
	s_and_b64 vcc, exec, s[68:69]
	v_ashrrev_i32_e32 v157, 31, v156
	s_cbranch_vccz .LBB0_3741
	v_pk_mul_f32 v[160:161], v[98:99], s[56:57] op_sel_hi:[1,0]
	v_pk_mul_f32 v[158:159], v[100:101], s[56:57] op_sel_hi:[1,0]
	v_bfe_u32 v138, v160, 16, 1
	v_add3_u32 v138, v160, v138, s78
	v_bfe_u32 v147, v161, 16, 1
	v_lshrrev_b32_e32 v138, 16, v138
	v_add3_u32 v147, v161, v147, s78
	v_and_or_b32 v160, v147, s79, v138
	v_bfe_u32 v138, v158, 16, 1
	v_add3_u32 v138, v158, v138, s78
	v_bfe_u32 v147, v159, 16, 1
	v_lshrrev_b32_e32 v138, 16, v138
	v_add3_u32 v147, v159, v147, s78
	v_and_or_b32 v161, v147, s79, v138
	v_lshl_add_u64 v[158:159], v[156:157], 1, v[164:165]
	global_store_dwordx2 v[158:159], v[160:161], off
.LBB0_3741:
	v_add_u32_e32 v162, 16, v154
	v_ashrrev_i32_e32 v138, 10, v162
	v_and_b32_e32 v181, -2, v138
	v_lshrrev_b32_e32 v138, 3, v162
	v_and_b32_e32 v155, 0xfe, v138
	v_and_b32_e32 v138, 0x1fff, v162
	v_ashrrev_i32_e32 v163, 31, v162
	v_cmp_lt_u32_e64 s[8:9], s77, v138
	v_add_u32_e32 v138, 0xffffe200, v138
	v_lshlrev_b64 v[160:161], 9, v[162:163]
	v_lshlrev_b64 v[158:159], 10, v[162:163]
	v_ashrrev_i32_e32 v162, 13, v162
	v_lshlrev_b64 v[164:165], 10, v[138:139]
	s_and_b64 vcc, exec, s[6:7]
	s_mov_b64 s[68:69], -1
	s_cbranch_vccnz .LBB0_3789
	v_bfe_u32 v138, v118, 16, 1
	v_add3_u32 v138, v118, v138, s78
	v_bfe_u32 v147, v119, 16, 1
	v_lshrrev_b32_e32 v138, 16, v138
	v_add3_u32 v147, v119, v147, s78
	v_and_or_b32 v166, v147, s79, v138
	v_bfe_u32 v138, v120, 16, 1
	v_add3_u32 v138, v120, v138, s78
	v_bfe_u32 v147, v121, 16, 1
	v_lshrrev_b32_e32 v138, 16, v138
	v_add3_u32 v147, v121, v147, s78
	v_and_or_b32 v167, v147, s79, v138
	s_cmp_lt_i32 s10, 3
	s_cbranch_scc1 .LBB0_3750
	s_cmp_lg_u32 s10, 3
	s_cbranch_scc0 .LBB0_3747
	v_lshlrev_b32_e32 v182, 1, v146
	v_lshl_add_u64 v[168:169], s[50:51], 0, v[160:161]
	v_ashrrev_i32_e32 v183, 31, v182
	v_lshl_add_u64 v[168:169], v[168:169], 0, v[182:183]
	global_store_dwordx2 v[168:169], v[166:167], off
	s_and_saveexec_b64 s[68:69], s[8:9]
	s_cbranch_execz .LBB0_3746
	v_ashrrev_i32_e32 v163, 31, v162
	v_lshlrev_b64 v[168:169], 19, v[162:163]
	v_lshl_add_u64 v[168:169], s[52:53], 0, v[168:169]
	v_lshl_add_u64 v[168:169], v[168:169], 0, v[164:165]
	v_ashrrev_i32_e32 v147, 31, v146
	v_lshl_add_u64 v[168:169], v[146:147], 2, v[168:169]
	v_add_co_u32_e32 v168, vcc, 0x100000, v168
	s_nop 1
	v_addc_co_u32_e32 v169, vcc, 0, v169, vcc
	global_store_dwordx4 v[168:169], v[118:121], off

.LBB0_3754:
	v_bfe_u32 v138, v114, 16, 1
	v_add3_u32 v138, v114, v138, s78
	v_bfe_u32 v147, v115, 16, 1
	v_lshrrev_b32_e32 v138, 16, v138
	v_add3_u32 v147, v115, v147, s78
	v_and_or_b32 v168, v147, s79, v138
	v_bfe_u32 v138, v116, 16, 1
	v_add3_u32 v138, v116, v138, s78
	v_bfe_u32 v147, v117, 16, 1
	v_lshrrev_b32_e32 v138, 16, v138
	v_add3_u32 v147, v117, v147, s78
	v_and_or_b32 v169, v147, s79, v138
	s_cmp_lt_i32 s10, 3
	s_cbranch_scc1 .LBB0_3762
	s_cmp_lg_u32 s10, 3
	s_cbranch_scc0 .LBB0_3759
	v_lshlrev_b32_e32 v184, 1, v178
	v_lshl_add_u64 v[182:183], s[50:51], 0, v[160:161]
	v_ashrrev_i32_e32 v185, 31, v184
	v_lshl_add_u64 v[182:183], v[182:183], 0, v[184:185]
	global_store_dwordx2 v[182:183], v[168:169], off
	s_and_saveexec_b64 s[68:69], s[8:9]
	s_cbranch_execz .LBB0_3758
	v_ashrrev_i32_e32 v163, 31, v162
	v_lshlrev_b64 v[182:183], 19, v[162:163]
	v_lshl_add_u64 v[182:183], s[52:53], 0, v[182:183]
	v_lshl_add_u64 v[182:183], v[182:183], 0, v[164:165]
	v_ashrrev_i32_e32 v147, 31, v146
	v_lshl_add_u64 v[182:183], v[146:147], 2, v[182:183]
	v_add_co_u32_e32 v182, vcc, 0x100000, v182
	s_nop 1
	v_addc_co_u32_e32 v183, vcc, 0, v183, vcc
	global_store_dwordx4 v[182:183], v[114:117], off offset:64

.LBB0_3766:
	v_bfe_u32 v138, v90, 16, 1
	v_add3_u32 v138, v90, v138, s78
	v_bfe_u32 v147, v91, 16, 1
	v_lshrrev_b32_e32 v138, 16, v138
	v_add3_u32 v147, v91, v147, s78
	v_and_or_b32 v168, v147, s79, v138
	v_bfe_u32 v138, v92, 16, 1
	v_add3_u32 v138, v92, v138, s78
	v_bfe_u32 v147, v93, 16, 1
	v_lshrrev_b32_e32 v138, 16, v138
	v_add3_u32 v147, v93, v147, s78
	v_and_or_b32 v169, v147, s79, v138
	s_cmp_lt_i32 s10, 3
	s_cbranch_scc1 .LBB0_3774
	s_cmp_lg_u32 s10, 3
	s_cbranch_scc0 .LBB0_3771
	v_lshlrev_b32_e32 v184, 1, v180
	v_lshl_add_u64 v[182:183], s[50:51], 0, v[160:161]
	v_ashrrev_i32_e32 v185, 31, v184
	v_lshl_add_u64 v[182:183], v[182:183], 0, v[184:185]
	global_store_dwordx2 v[182:183], v[168:169], off
	s_and_saveexec_b64 s[68:69], s[8:9]
	s_cbranch_execz .LBB0_3770
	v_ashrrev_i32_e32 v163, 31, v162
	v_lshlrev_b64 v[182:183], 19, v[162:163]
	v_lshl_add_u64 v[182:183], s[52:53], 0, v[182:183]
	v_lshl_add_u64 v[182:183], v[182:183], 0, v[164:165]
	v_ashrrev_i32_e32 v147, 31, v146
	v_lshl_add_u64 v[182:183], v[146:147], 2, v[182:183]
	v_add_co_u32_e32 v182, vcc, 0x100000, v182
	s_nop 1
	v_addc_co_u32_e32 v183, vcc, 0, v183, vcc
	global_store_dwordx4 v[182:183], v[90:93], off offset:512

.LBB0_3778:
	v_bfe_u32 v138, v82, 16, 1
	v_add3_u32 v138, v82, v138, s78
	v_bfe_u32 v147, v83, 16, 1
	v_lshrrev_b32_e32 v138, 16, v138
	v_add3_u32 v147, v83, v147, s78
	v_and_or_b32 v168, v147, s79, v138
	v_bfe_u32 v138, v84, 16, 1
	v_add3_u32 v138, v84, v138, s78
	v_bfe_u32 v147, v85, 16, 1
	v_lshrrev_b32_e32 v138, 16, v138
	v_add3_u32 v147, v85, v147, s78
	v_and_or_b32 v169, v147, s79, v138
	s_cmp_lt_i32 s10, 3
	s_cbranch_scc1 .LBB0_3786
	s_cmp_lg_u32 s10, 3
	s_cbranch_scc0 .LBB0_3783
	v_lshlrev_b32_e32 v184, 1, v179
	v_lshl_add_u64 v[182:183], s[50:51], 0, v[160:161]
	v_ashrrev_i32_e32 v185, 31, v184
	v_lshl_add_u64 v[182:183], v[182:183], 0, v[184:185]
	global_store_dwordx2 v[182:183], v[168:169], off
	s_and_saveexec_b64 s[68:69], s[8:9]
	s_cbranch_execz .LBB0_3782
	v_ashrrev_i32_e32 v163, 31, v162
	v_lshlrev_b64 v[162:163], 19, v[162:163]
	v_lshl_add_u64 v[162:163], s[52:53], 0, v[162:163]
	v_lshl_add_u64 v[162:163], v[162:163], 0, v[164:165]
	v_ashrrev_i32_e32 v147, 31, v146
	v_lshl_add_u64 v[162:163], v[146:147], 2, v[162:163]
	v_add_co_u32_e32 v162, vcc, 0x100000, v162
	s_nop 1
	v_addc_co_u32_e32 v163, vcc, 0, v163, vcc
	global_store_dwordx4 v[162:163], v[82:85], off offset:576

.LBB0_3789:
	s_and_b64 vcc, exec, s[68:69]
	v_lshl_add_u64 v[166:167], s[54:55], 0, v[158:159]
	s_cbranch_vccz .LBB0_3753
	v_pk_mul_f32 v[182:183], v[118:119], s[56:57] op_sel_hi:[1,0]
	v_pk_mul_f32 v[168:169], v[120:121], s[56:57] op_sel_hi:[1,0]
	v_bfe_u32 v138, v182, 16, 1
	v_add3_u32 v138, v182, v138, s78
	v_bfe_u32 v147, v183, 16, 1
	v_lshrrev_b32_e32 v138, 16, v138
	v_add3_u32 v147, v183, v147, s78
	v_and_or_b32 v182, v147, s79, v138
	v_bfe_u32 v138, v168, 16, 1
	v_add3_u32 v138, v168, v138, s78
	v_bfe_u32 v147, v169, 16, 1
	v_lshrrev_b32_e32 v138, 16, v138
	v_add3_u32 v147, v169, v147, s78
	v_and_or_b32 v183, v147, s79, v138
	v_lshl_add_u64 v[168:169], v[148:149], 1, v[166:167]
	global_store_dwordx2 v[168:169], v[182:183], off
	s_and_b64 vcc, exec, s[6:7]
	s_mov_b64 s[68:69], -1
	s_cbranch_vccz .LBB0_3754
.LBB0_3791:
	s_and_b64 vcc, exec, s[68:69]
	s_cbranch_vccz .LBB0_3765
	v_pk_mul_f32 v[182:183], v[114:115], s[56:57] op_sel_hi:[1,0]
	v_pk_mul_f32 v[168:169], v[116:117], s[56:57] op_sel_hi:[1,0]
	v_bfe_u32 v138, v182, 16, 1
	v_add3_u32 v138, v182, v138, s78
	v_bfe_u32 v147, v183, 16, 1
	v_lshrrev_b32_e32 v138, 16, v138
	v_add3_u32 v147, v183, v147, s78
	v_and_or_b32 v182, v147, s79, v138
	v_bfe_u32 v138, v168, 16, 1
	v_add3_u32 v138, v168, v138, s78
	v_bfe_u32 v147, v169, 16, 1
	v_lshrrev_b32_e32 v138, 16, v138
	v_add3_u32 v147, v169, v147, s78
	v_and_or_b32 v183, v147, s79, v138
	v_lshl_add_u64 v[168:169], v[150:151], 1, v[166:167]
	global_store_dwordx2 v[168:169], v[182:183], off
	s_and_b64 vcc, exec, s[6:7]
	s_mov_b64 s[68:69], -1
	s_cbranch_vccz .LBB0_3766
.LBB0_3793:
	s_and_b64 vcc, exec, s[68:69]
	s_cbranch_vccz .LBB0_3777
	v_pk_mul_f32 v[182:183], v[90:91], s[56:57] op_sel_hi:[1,0]
	v_pk_mul_f32 v[168:169], v[92:93], s[56:57] op_sel_hi:[1,0]
	v_bfe_u32 v138, v182, 16, 1
	v_add3_u32 v138, v182, v138, s78
	v_bfe_u32 v147, v183, 16, 1
	v_lshrrev_b32_e32 v138, 16, v138
	v_add3_u32 v147, v183, v147, s78
	v_and_or_b32 v182, v147, s79, v138
	v_bfe_u32 v138, v168, 16, 1
	v_add3_u32 v138, v168, v138, s78
	v_bfe_u32 v147, v169, 16, 1
	v_lshrrev_b32_e32 v138, 16, v138
	v_add3_u32 v147, v169, v147, s78
	v_and_or_b32 v183, v147, s79, v138
	v_lshl_add_u64 v[168:169], v[152:153], 1, v[166:167]
	global_store_dwordx2 v[168:169], v[182:183], off
	s_and_b64 vcc, exec, s[6:7]
	s_mov_b64 s[68:69], -1
	s_cbranch_vccz .LBB0_3778
.LBB0_3795:
	s_and_b64 vcc, exec, s[68:69]
	s_cbranch_vccz .LBB0_3797
	v_pk_mul_f32 v[160:161], v[82:83], s[56:57] op_sel_hi:[1,0]
	v_pk_mul_f32 v[158:159], v[84:85], s[56:57] op_sel_hi:[1,0]
	v_bfe_u32 v138, v160, 16, 1
	v_add3_u32 v138, v160, v138, s78
	v_bfe_u32 v147, v161, 16, 1
	v_lshrrev_b32_e32 v138, 16, v138
	v_add3_u32 v147, v161, v147, s78
	v_and_or_b32 v160, v147, s79, v138
	v_bfe_u32 v138, v158, 16, 1
	v_add3_u32 v138, v158, v138, s78
	v_bfe_u32 v147, v159, 16, 1
	v_lshrrev_b32_e32 v138, 16, v138
	v_add3_u32 v147, v159, v147, s78
	v_and_or_b32 v161, v147, s79, v138
	v_lshl_add_u64 v[158:159], v[156:157], 1, v[166:167]
	global_store_dwordx2 v[158:159], v[160:161], off
.LBB0_3797:
	v_add_u32_e32 v162, 32, v154
	v_ashrrev_i32_e32 v138, 10, v162
	v_and_b32_e32 v181, -2, v138
	v_lshrrev_b32_e32 v138, 3, v162
	v_and_b32_e32 v155, 0xfe, v138
	v_and_b32_e32 v138, 0x1fff, v162
	v_ashrrev_i32_e32 v163, 31, v162
	v_cmp_lt_u32_e64 s[8:9], s77, v138
	v_add_u32_e32 v138, 0xffffe200, v138
	v_lshlrev_b64 v[160:161], 9, v[162:163]
	v_lshlrev_b64 v[158:159], 10, v[162:163]
	v_ashrrev_i32_e32 v162, 13, v162
	v_lshlrev_b64 v[164:165], 10, v[138:139]
	s_and_b64 vcc, exec, s[6:7]
	s_mov_b64 s[68:69], -1
	s_cbranch_vccnz .LBB0_3845
	v_bfe_u32 v138, v110, 16, 1
	v_add3_u32 v138, v110, v138, s78
	v_bfe_u32 v147, v111, 16, 1
	v_lshrrev_b32_e32 v138, 16, v138
	v_add3_u32 v147, v111, v147, s78
	v_and_or_b32 v166, v147, s79, v138
	v_bfe_u32 v138, v112, 16, 1
	v_add3_u32 v138, v112, v138, s78
	v_bfe_u32 v147, v113, 16, 1
	v_lshrrev_b32_e32 v138, 16, v138
	v_add3_u32 v147, v113, v147, s78
	v_and_or_b32 v167, v147, s79, v138
	s_cmp_lt_i32 s10, 3
	s_cbranch_scc1 .LBB0_3806
	s_cmp_lg_u32 s10, 3
	s_cbranch_scc0 .LBB0_3803
	v_lshlrev_b32_e32 v182, 1, v146
	v_lshl_add_u64 v[168:169], s[50:51], 0, v[160:161]
	v_ashrrev_i32_e32 v183, 31, v182
	v_lshl_add_u64 v[168:169], v[168:169], 0, v[182:183]
	global_store_dwordx2 v[168:169], v[166:167], off
	s_and_saveexec_b64 s[68:69], s[8:9]
	s_cbranch_execz .LBB0_3802
	v_ashrrev_i32_e32 v163, 31, v162
	v_lshlrev_b64 v[168:169], 19, v[162:163]
	v_lshl_add_u64 v[168:169], s[52:53], 0, v[168:169]
	v_lshl_add_u64 v[168:169], v[168:169], 0, v[164:165]
	v_ashrrev_i32_e32 v147, 31, v146
	v_lshl_add_u64 v[168:169], v[146:147], 2, v[168:169]
	v_add_co_u32_e32 v168, vcc, 0x100000, v168
	s_nop 1
	v_addc_co_u32_e32 v169, vcc, 0, v169, vcc
	global_store_dwordx4 v[168:169], v[110:113], off

.LBB0_3810:
	v_bfe_u32 v138, v102, 16, 1
	v_add3_u32 v138, v102, v138, s78
	v_bfe_u32 v147, v103, 16, 1
	v_lshrrev_b32_e32 v138, 16, v138
	v_add3_u32 v147, v103, v147, s78
	v_and_or_b32 v168, v147, s79, v138
	v_bfe_u32 v138, v104, 16, 1
	v_add3_u32 v138, v104, v138, s78
	v_bfe_u32 v147, v105, 16, 1
	v_lshrrev_b32_e32 v138, 16, v138
	v_add3_u32 v147, v105, v147, s78
	v_and_or_b32 v169, v147, s79, v138
	s_cmp_lt_i32 s10, 3
	s_cbranch_scc1 .LBB0_3818
	s_cmp_lg_u32 s10, 3
	s_cbranch_scc0 .LBB0_3815
	v_lshlrev_b32_e32 v184, 1, v178
	v_lshl_add_u64 v[182:183], s[50:51], 0, v[160:161]
	v_ashrrev_i32_e32 v185, 31, v184
	v_lshl_add_u64 v[182:183], v[182:183], 0, v[184:185]
	global_store_dwordx2 v[182:183], v[168:169], off
	s_and_saveexec_b64 s[68:69], s[8:9]
	s_cbranch_execz .LBB0_3814
	v_ashrrev_i32_e32 v163, 31, v162
	v_lshlrev_b64 v[182:183], 19, v[162:163]
	v_lshl_add_u64 v[182:183], s[52:53], 0, v[182:183]
	v_lshl_add_u64 v[182:183], v[182:183], 0, v[164:165]
	v_ashrrev_i32_e32 v147, 31, v146
	v_lshl_add_u64 v[182:183], v[146:147], 2, v[182:183]
	v_add_co_u32_e32 v182, vcc, 0x100000, v182
	s_nop 1
	v_addc_co_u32_e32 v183, vcc, 0, v183, vcc
	global_store_dwordx4 v[182:183], v[102:105], off offset:64

.LBB0_3822:
	v_bfe_u32 v138, v78, 16, 1
	v_add3_u32 v138, v78, v138, s78
	v_bfe_u32 v147, v79, 16, 1
	v_lshrrev_b32_e32 v138, 16, v138
	v_add3_u32 v147, v79, v147, s78
	v_and_or_b32 v168, v147, s79, v138
	v_bfe_u32 v138, v80, 16, 1
	v_add3_u32 v138, v80, v138, s78
	v_bfe_u32 v147, v81, 16, 1
	v_lshrrev_b32_e32 v138, 16, v138
	v_add3_u32 v147, v81, v147, s78
	v_and_or_b32 v169, v147, s79, v138
	s_cmp_lt_i32 s10, 3
	s_cbranch_scc1 .LBB0_3830
	s_cmp_lg_u32 s10, 3
	s_cbranch_scc0 .LBB0_3827
	v_lshlrev_b32_e32 v184, 1, v180
	v_lshl_add_u64 v[182:183], s[50:51], 0, v[160:161]
	v_ashrrev_i32_e32 v185, 31, v184
	v_lshl_add_u64 v[182:183], v[182:183], 0, v[184:185]
	global_store_dwordx2 v[182:183], v[168:169], off
	s_and_saveexec_b64 s[68:69], s[8:9]
	s_cbranch_execz .LBB0_3826
	v_ashrrev_i32_e32 v163, 31, v162
	v_lshlrev_b64 v[182:183], 19, v[162:163]
	v_lshl_add_u64 v[182:183], s[52:53], 0, v[182:183]
	v_lshl_add_u64 v[182:183], v[182:183], 0, v[164:165]
	v_ashrrev_i32_e32 v147, 31, v146
	v_lshl_add_u64 v[182:183], v[146:147], 2, v[182:183]
	v_add_co_u32_e32 v182, vcc, 0x100000, v182
	s_nop 1
	v_addc_co_u32_e32 v183, vcc, 0, v183, vcc
	global_store_dwordx4 v[182:183], v[78:81], off offset:512

.LBB0_3834:
	v_bfe_u32 v138, v74, 16, 1
	v_add3_u32 v138, v74, v138, s78
	v_bfe_u32 v147, v75, 16, 1
	v_lshrrev_b32_e32 v138, 16, v138
	v_add3_u32 v147, v75, v147, s78
	v_and_or_b32 v168, v147, s79, v138
	v_bfe_u32 v138, v76, 16, 1
	v_add3_u32 v138, v76, v138, s78
	v_bfe_u32 v147, v77, 16, 1
	v_lshrrev_b32_e32 v138, 16, v138
	v_add3_u32 v147, v77, v147, s78
	v_and_or_b32 v169, v147, s79, v138
	s_cmp_lt_i32 s10, 3
	s_cbranch_scc1 .LBB0_3842
	s_cmp_lg_u32 s10, 3
	s_cbranch_scc0 .LBB0_3839
	v_lshlrev_b32_e32 v184, 1, v179
	v_lshl_add_u64 v[182:183], s[50:51], 0, v[160:161]
	v_ashrrev_i32_e32 v185, 31, v184
	v_lshl_add_u64 v[182:183], v[182:183], 0, v[184:185]
	global_store_dwordx2 v[182:183], v[168:169], off
	s_and_saveexec_b64 s[68:69], s[8:9]
	s_cbranch_execz .LBB0_3838
	v_ashrrev_i32_e32 v163, 31, v162
	v_lshlrev_b64 v[162:163], 19, v[162:163]
	v_lshl_add_u64 v[162:163], s[52:53], 0, v[162:163]
	v_lshl_add_u64 v[162:163], v[162:163], 0, v[164:165]
	v_ashrrev_i32_e32 v147, 31, v146
	v_lshl_add_u64 v[162:163], v[146:147], 2, v[162:163]
	v_add_co_u32_e32 v162, vcc, 0x100000, v162
	s_nop 1
	v_addc_co_u32_e32 v163, vcc, 0, v163, vcc
	global_store_dwordx4 v[162:163], v[74:77], off offset:576

.LBB0_3845:
	s_and_b64 vcc, exec, s[68:69]
	v_lshl_add_u64 v[166:167], s[54:55], 0, v[158:159]
	s_cbranch_vccz .LBB0_3809
	v_pk_mul_f32 v[182:183], v[110:111], s[56:57] op_sel_hi:[1,0]
	v_pk_mul_f32 v[168:169], v[112:113], s[56:57] op_sel_hi:[1,0]
	v_bfe_u32 v138, v182, 16, 1
	v_add3_u32 v138, v182, v138, s78
	v_bfe_u32 v147, v183, 16, 1
	v_lshrrev_b32_e32 v138, 16, v138
	v_add3_u32 v147, v183, v147, s78
	v_and_or_b32 v182, v147, s79, v138
	v_bfe_u32 v138, v168, 16, 1
	v_add3_u32 v138, v168, v138, s78
	v_bfe_u32 v147, v169, 16, 1
	v_lshrrev_b32_e32 v138, 16, v138
	v_add3_u32 v147, v169, v147, s78
	v_and_or_b32 v183, v147, s79, v138
	v_lshl_add_u64 v[168:169], v[148:149], 1, v[166:167]
	global_store_dwordx2 v[168:169], v[182:183], off
	s_and_b64 vcc, exec, s[6:7]
	s_mov_b64 s[68:69], -1
	s_cbranch_vccz .LBB0_3810
.LBB0_3847:
	s_and_b64 vcc, exec, s[68:69]
	s_cbranch_vccz .LBB0_3821
	v_pk_mul_f32 v[182:183], v[102:103], s[56:57] op_sel_hi:[1,0]
	v_pk_mul_f32 v[168:169], v[104:105], s[56:57] op_sel_hi:[1,0]
	v_bfe_u32 v138, v182, 16, 1
	v_add3_u32 v138, v182, v138, s78
	v_bfe_u32 v147, v183, 16, 1
	v_lshrrev_b32_e32 v138, 16, v138
	v_add3_u32 v147, v183, v147, s78
	v_and_or_b32 v182, v147, s79, v138
	v_bfe_u32 v138, v168, 16, 1
	v_add3_u32 v138, v168, v138, s78
	v_bfe_u32 v147, v169, 16, 1
	v_lshrrev_b32_e32 v138, 16, v138
	v_add3_u32 v147, v169, v147, s78
	v_and_or_b32 v183, v147, s79, v138
	v_lshl_add_u64 v[168:169], v[150:151], 1, v[166:167]
	global_store_dwordx2 v[168:169], v[182:183], off
	s_and_b64 vcc, exec, s[6:7]
	s_mov_b64 s[68:69], -1
	s_cbranch_vccz .LBB0_3822
.LBB0_3849:
	s_and_b64 vcc, exec, s[68:69]
	s_cbranch_vccz .LBB0_3833
	v_pk_mul_f32 v[182:183], v[78:79], s[56:57] op_sel_hi:[1,0]
	v_pk_mul_f32 v[168:169], v[80:81], s[56:57] op_sel_hi:[1,0]
	v_bfe_u32 v138, v182, 16, 1
	v_add3_u32 v138, v182, v138, s78
	v_bfe_u32 v147, v183, 16, 1
	v_lshrrev_b32_e32 v138, 16, v138
	v_add3_u32 v147, v183, v147, s78
	v_and_or_b32 v182, v147, s79, v138
	v_bfe_u32 v138, v168, 16, 1
	v_add3_u32 v138, v168, v138, s78
	v_bfe_u32 v147, v169, 16, 1
	v_lshrrev_b32_e32 v138, 16, v138
	v_add3_u32 v147, v169, v147, s78
	v_and_or_b32 v183, v147, s79, v138
	v_lshl_add_u64 v[168:169], v[152:153], 1, v[166:167]
	global_store_dwordx2 v[168:169], v[182:183], off
	s_and_b64 vcc, exec, s[6:7]
	s_mov_b64 s[68:69], -1
	s_cbranch_vccz .LBB0_3834
.LBB0_3851:
	s_and_b64 vcc, exec, s[68:69]
	s_cbranch_vccz .LBB0_3853
	v_pk_mul_f32 v[160:161], v[74:75], s[56:57] op_sel_hi:[1,0]
	v_pk_mul_f32 v[158:159], v[76:77], s[56:57] op_sel_hi:[1,0]
	v_bfe_u32 v138, v160, 16, 1
	v_add3_u32 v138, v160, v138, s78
	v_bfe_u32 v147, v161, 16, 1
	v_lshrrev_b32_e32 v138, 16, v138
	v_add3_u32 v147, v161, v147, s78
	v_and_or_b32 v160, v147, s79, v138
	v_bfe_u32 v138, v158, 16, 1
	v_add3_u32 v138, v158, v138, s78
	v_bfe_u32 v147, v159, 16, 1
	v_lshrrev_b32_e32 v138, 16, v138
	v_add3_u32 v147, v159, v147, s78
	v_and_or_b32 v161, v147, s79, v138
	v_lshl_add_u64 v[158:159], v[156:157], 1, v[166:167]
	global_store_dwordx2 v[158:159], v[160:161], off
.LBB0_3853:
	v_add_u32_e32 v162, 48, v154
	v_ashrrev_i32_e32 v138, 10, v162
	v_and_b32_e32 v181, -2, v138
	v_lshrrev_b32_e32 v138, 3, v162
	v_and_b32_e32 v155, 0xfe, v138
	v_and_b32_e32 v138, 0x1fff, v162
	v_ashrrev_i32_e32 v163, 31, v162
	v_cmp_lt_u32_e64 s[8:9], s77, v138
	v_add_u32_e32 v138, 0xffffe200, v138
	v_lshlrev_b64 v[160:161], 9, v[162:163]
	v_lshlrev_b64 v[158:159], 10, v[162:163]
	v_ashrrev_i32_e32 v162, 13, v162
	v_lshlrev_b64 v[164:165], 10, v[138:139]
	s_and_b64 vcc, exec, s[6:7]
	s_mov_b64 s[68:69], -1
	s_cbranch_vccnz .LBB0_3901
	v_bfe_u32 v138, v94, 16, 1
	v_add3_u32 v138, v94, v138, s78
	v_bfe_u32 v147, v95, 16, 1
	v_lshrrev_b32_e32 v138, 16, v138
	v_add3_u32 v147, v95, v147, s78
	v_and_or_b32 v166, v147, s79, v138
	v_bfe_u32 v138, v96, 16, 1
	v_add3_u32 v138, v96, v138, s78
	v_bfe_u32 v147, v97, 16, 1
	v_lshrrev_b32_e32 v138, 16, v138
	v_add3_u32 v147, v97, v147, s78
	v_and_or_b32 v167, v147, s79, v138
	s_cmp_lt_i32 s10, 3
	s_cbranch_scc1 .LBB0_3862
	s_cmp_lg_u32 s10, 3
	s_cbranch_scc0 .LBB0_3859
	v_lshlrev_b32_e32 v182, 1, v146
	v_lshl_add_u64 v[168:169], s[50:51], 0, v[160:161]
	v_ashrrev_i32_e32 v183, 31, v182
	v_lshl_add_u64 v[168:169], v[168:169], 0, v[182:183]
	global_store_dwordx2 v[168:169], v[166:167], off
	s_and_saveexec_b64 s[68:69], s[8:9]
	s_cbranch_execz .LBB0_3858
	v_ashrrev_i32_e32 v163, 31, v162
	v_lshlrev_b64 v[168:169], 19, v[162:163]
	v_lshl_add_u64 v[168:169], s[52:53], 0, v[168:169]
	v_lshl_add_u64 v[168:169], v[168:169], 0, v[164:165]
	v_ashrrev_i32_e32 v147, 31, v146
	v_lshl_add_u64 v[168:169], v[146:147], 2, v[168:169]
	v_add_co_u32_e32 v168, vcc, 0x100000, v168
	s_nop 1
	v_addc_co_u32_e32 v169, vcc, 0, v169, vcc
	global_store_dwordx4 v[168:169], v[94:97], off

.LBB0_3866:
	v_bfe_u32 v138, v86, 16, 1
	v_add3_u32 v138, v86, v138, s78
	v_bfe_u32 v147, v87, 16, 1
	v_lshrrev_b32_e32 v138, 16, v138
	v_add3_u32 v147, v87, v147, s78
	v_and_or_b32 v168, v147, s79, v138
	v_bfe_u32 v138, v88, 16, 1
	v_add3_u32 v138, v88, v138, s78
	v_bfe_u32 v147, v89, 16, 1
	v_lshrrev_b32_e32 v138, 16, v138
	v_add3_u32 v147, v89, v147, s78
	v_and_or_b32 v169, v147, s79, v138
	s_cmp_lt_i32 s10, 3
	s_cbranch_scc1 .LBB0_3874
	s_cmp_lg_u32 s10, 3
	s_cbranch_scc0 .LBB0_3871
	v_lshlrev_b32_e32 v184, 1, v178
	v_lshl_add_u64 v[182:183], s[50:51], 0, v[160:161]
	v_ashrrev_i32_e32 v185, 31, v184
	v_lshl_add_u64 v[182:183], v[182:183], 0, v[184:185]
	global_store_dwordx2 v[182:183], v[168:169], off
	s_and_saveexec_b64 s[68:69], s[8:9]
	s_cbranch_execz .LBB0_3870
	v_ashrrev_i32_e32 v163, 31, v162
	v_lshlrev_b64 v[182:183], 19, v[162:163]
	v_lshl_add_u64 v[182:183], s[52:53], 0, v[182:183]
	v_lshl_add_u64 v[182:183], v[182:183], 0, v[164:165]
	v_ashrrev_i32_e32 v147, 31, v146
	v_lshl_add_u64 v[182:183], v[146:147], 2, v[182:183]
	v_add_co_u32_e32 v182, vcc, 0x100000, v182
	s_nop 1
	v_addc_co_u32_e32 v183, vcc, 0, v183, vcc
	global_store_dwordx4 v[182:183], v[86:89], off offset:64

.LBB0_3878:
	v_bfe_u32 v138, v70, 16, 1
	v_add3_u32 v138, v70, v138, s78
	v_bfe_u32 v147, v71, 16, 1
	v_lshrrev_b32_e32 v138, 16, v138
	v_add3_u32 v147, v71, v147, s78
	v_and_or_b32 v168, v147, s79, v138
	v_bfe_u32 v138, v72, 16, 1
	v_add3_u32 v138, v72, v138, s78
	v_bfe_u32 v147, v73, 16, 1
	v_lshrrev_b32_e32 v138, 16, v138
	v_add3_u32 v147, v73, v147, s78
	v_and_or_b32 v169, v147, s79, v138
	s_cmp_lt_i32 s10, 3
	s_cbranch_scc1 .LBB0_3886
	s_cmp_lg_u32 s10, 3
	s_cbranch_scc0 .LBB0_3883
	v_lshlrev_b32_e32 v184, 1, v180
	v_lshl_add_u64 v[182:183], s[50:51], 0, v[160:161]
	v_ashrrev_i32_e32 v185, 31, v184
	v_lshl_add_u64 v[182:183], v[182:183], 0, v[184:185]
	global_store_dwordx2 v[182:183], v[168:169], off
	s_and_saveexec_b64 s[68:69], s[8:9]
	s_cbranch_execz .LBB0_3882
	v_ashrrev_i32_e32 v163, 31, v162
	v_lshlrev_b64 v[182:183], 19, v[162:163]
	v_lshl_add_u64 v[182:183], s[52:53], 0, v[182:183]
	v_lshl_add_u64 v[182:183], v[182:183], 0, v[164:165]
	v_ashrrev_i32_e32 v147, 31, v146
	v_lshl_add_u64 v[182:183], v[146:147], 2, v[182:183]
	v_add_co_u32_e32 v182, vcc, 0x100000, v182
	s_nop 1
	v_addc_co_u32_e32 v183, vcc, 0, v183, vcc
	global_store_dwordx4 v[182:183], v[70:73], off offset:512

.LBB0_3890:
	v_bfe_u32 v138, v66, 16, 1
	v_add3_u32 v138, v66, v138, s78
	v_bfe_u32 v147, v67, 16, 1
	v_lshrrev_b32_e32 v138, 16, v138
	v_add3_u32 v147, v67, v147, s78
	v_and_or_b32 v168, v147, s79, v138
	v_bfe_u32 v138, v68, 16, 1
	v_add3_u32 v138, v68, v138, s78
	v_bfe_u32 v147, v69, 16, 1
	v_lshrrev_b32_e32 v138, 16, v138
	v_add3_u32 v147, v69, v147, s78
	v_and_or_b32 v169, v147, s79, v138
	s_cmp_lt_i32 s10, 3
	s_cbranch_scc1 .LBB0_3898
	s_cmp_lg_u32 s10, 3
	s_cbranch_scc0 .LBB0_3895
	v_lshlrev_b32_e32 v184, 1, v179
	v_lshl_add_u64 v[182:183], s[50:51], 0, v[160:161]
	v_ashrrev_i32_e32 v185, 31, v184
	v_lshl_add_u64 v[182:183], v[182:183], 0, v[184:185]
	global_store_dwordx2 v[182:183], v[168:169], off
	s_and_saveexec_b64 s[68:69], s[8:9]
	s_cbranch_execz .LBB0_3894
	v_ashrrev_i32_e32 v163, 31, v162
	v_lshlrev_b64 v[162:163], 19, v[162:163]
	v_lshl_add_u64 v[162:163], s[52:53], 0, v[162:163]
	v_lshl_add_u64 v[162:163], v[162:163], 0, v[164:165]
	v_ashrrev_i32_e32 v147, 31, v146
	v_lshl_add_u64 v[162:163], v[146:147], 2, v[162:163]
	v_add_co_u32_e32 v162, vcc, 0x100000, v162
	s_nop 1
	v_addc_co_u32_e32 v163, vcc, 0, v163, vcc
	global_store_dwordx4 v[162:163], v[66:69], off offset:576

.LBB0_3901:
	s_and_b64 vcc, exec, s[68:69]
	v_lshl_add_u64 v[166:167], s[54:55], 0, v[158:159]
	s_cbranch_vccz .LBB0_3865
	v_pk_mul_f32 v[182:183], v[94:95], s[56:57] op_sel_hi:[1,0]
	v_pk_mul_f32 v[168:169], v[96:97], s[56:57] op_sel_hi:[1,0]
	v_bfe_u32 v138, v182, 16, 1
	v_add3_u32 v138, v182, v138, s78
	v_bfe_u32 v147, v183, 16, 1
	v_lshrrev_b32_e32 v138, 16, v138
	v_add3_u32 v147, v183, v147, s78
	v_and_or_b32 v182, v147, s79, v138
	v_bfe_u32 v138, v168, 16, 1
	v_add3_u32 v138, v168, v138, s78
	v_bfe_u32 v147, v169, 16, 1
	v_lshrrev_b32_e32 v138, 16, v138
	v_add3_u32 v147, v169, v147, s78
	v_and_or_b32 v183, v147, s79, v138
	v_lshl_add_u64 v[168:169], v[148:149], 1, v[166:167]
	global_store_dwordx2 v[168:169], v[182:183], off
	s_and_b64 vcc, exec, s[6:7]
	s_mov_b64 s[68:69], -1
	s_cbranch_vccz .LBB0_3866
.LBB0_3903:
	s_and_b64 vcc, exec, s[68:69]
	s_cbranch_vccz .LBB0_3877
	v_pk_mul_f32 v[182:183], v[86:87], s[56:57] op_sel_hi:[1,0]
	v_pk_mul_f32 v[168:169], v[88:89], s[56:57] op_sel_hi:[1,0]
	v_bfe_u32 v138, v182, 16, 1
	v_add3_u32 v138, v182, v138, s78
	v_bfe_u32 v147, v183, 16, 1
	v_lshrrev_b32_e32 v138, 16, v138
	v_add3_u32 v147, v183, v147, s78
	v_and_or_b32 v182, v147, s79, v138
	v_bfe_u32 v138, v168, 16, 1
	v_add3_u32 v138, v168, v138, s78
	v_bfe_u32 v147, v169, 16, 1
	v_lshrrev_b32_e32 v138, 16, v138
	v_add3_u32 v147, v169, v147, s78
	v_and_or_b32 v183, v147, s79, v138
	v_lshl_add_u64 v[168:169], v[150:151], 1, v[166:167]
	global_store_dwordx2 v[168:169], v[182:183], off
	s_and_b64 vcc, exec, s[6:7]
	s_mov_b64 s[68:69], -1
	s_cbranch_vccz .LBB0_3878
.LBB0_3905:
	s_and_b64 vcc, exec, s[68:69]
	s_cbranch_vccz .LBB0_3889
	v_pk_mul_f32 v[182:183], v[70:71], s[56:57] op_sel_hi:[1,0]
	v_pk_mul_f32 v[168:169], v[72:73], s[56:57] op_sel_hi:[1,0]
	v_bfe_u32 v138, v182, 16, 1
	v_add3_u32 v138, v182, v138, s78
	v_bfe_u32 v147, v183, 16, 1
	v_lshrrev_b32_e32 v138, 16, v138
	v_add3_u32 v147, v183, v147, s78
	v_and_or_b32 v182, v147, s79, v138
	v_bfe_u32 v138, v168, 16, 1
	v_add3_u32 v138, v168, v138, s78
	v_bfe_u32 v147, v169, 16, 1
	v_lshrrev_b32_e32 v138, 16, v138
	v_add3_u32 v147, v169, v147, s78
	v_and_or_b32 v183, v147, s79, v138
	v_lshl_add_u64 v[168:169], v[152:153], 1, v[166:167]
	global_store_dwordx2 v[168:169], v[182:183], off
	s_and_b64 vcc, exec, s[6:7]
	s_mov_b64 s[68:69], -1
	s_cbranch_vccz .LBB0_3890
.LBB0_3907:
	s_and_b64 vcc, exec, s[68:69]
	s_cbranch_vccz .LBB0_3909
	v_pk_mul_f32 v[160:161], v[66:67], s[56:57] op_sel_hi:[1,0]
	v_pk_mul_f32 v[158:159], v[68:69], s[56:57] op_sel_hi:[1,0]
	v_bfe_u32 v138, v160, 16, 1
	v_add3_u32 v138, v160, v138, s78
	v_bfe_u32 v147, v161, 16, 1
	v_lshrrev_b32_e32 v138, 16, v138
	v_add3_u32 v147, v161, v147, s78
	v_and_or_b32 v160, v147, s79, v138
	v_bfe_u32 v138, v158, 16, 1
	v_add3_u32 v138, v158, v138, s78
	v_bfe_u32 v147, v159, 16, 1
	v_lshrrev_b32_e32 v138, 16, v138
	v_add3_u32 v147, v159, v147, s78
	v_and_or_b32 v161, v147, s79, v138
	v_lshl_add_u64 v[158:159], v[156:157], 1, v[166:167]
	global_store_dwordx2 v[158:159], v[160:161], off
.LBB0_3909:
	v_add_u32_e32 v162, 0x80, v154
	v_ashrrev_i32_e32 v138, 10, v162
	v_and_b32_e32 v181, -2, v138
	v_lshrrev_b32_e32 v138, 3, v162
	v_and_b32_e32 v155, 0xfe, v138
	v_and_b32_e32 v138, 0x1fff, v162
	v_ashrrev_i32_e32 v163, 31, v162
	v_cmp_lt_u32_e64 s[8:9], s77, v138
	v_add_u32_e32 v138, 0xffffe200, v138
	v_lshlrev_b64 v[160:161], 9, v[162:163]
	v_lshlrev_b64 v[158:159], 10, v[162:163]
	v_ashrrev_i32_e32 v162, 13, v162
	v_lshlrev_b64 v[164:165], 10, v[138:139]
	s_and_b64 vcc, exec, s[6:7]
	s_mov_b64 s[68:69], -1
	s_cbranch_vccnz .LBB0_3957
	v_bfe_u32 v138, v62, 16, 1
	v_add3_u32 v138, v62, v138, s78
	v_bfe_u32 v147, v63, 16, 1
	v_lshrrev_b32_e32 v138, 16, v138
	v_add3_u32 v147, v63, v147, s78
	v_and_or_b32 v166, v147, s79, v138
	v_bfe_u32 v138, v64, 16, 1
	v_add3_u32 v138, v64, v138, s78
	v_bfe_u32 v147, v65, 16, 1
	v_lshrrev_b32_e32 v138, 16, v138
	v_add3_u32 v147, v65, v147, s78
	v_and_or_b32 v167, v147, s79, v138
	s_cmp_lt_i32 s10, 3
	s_cbranch_scc1 .LBB0_3918
	s_cmp_lg_u32 s10, 3
	s_cbranch_scc0 .LBB0_3915
	v_lshlrev_b32_e32 v182, 1, v146
	v_lshl_add_u64 v[168:169], s[50:51], 0, v[160:161]
	v_ashrrev_i32_e32 v183, 31, v182
	v_lshl_add_u64 v[168:169], v[168:169], 0, v[182:183]
	global_store_dwordx2 v[168:169], v[166:167], off
	s_and_saveexec_b64 s[68:69], s[8:9]
	s_cbranch_execz .LBB0_3914
	v_ashrrev_i32_e32 v163, 31, v162
	v_lshlrev_b64 v[168:169], 19, v[162:163]
	v_lshl_add_u64 v[168:169], s[52:53], 0, v[168:169]
	v_lshl_add_u64 v[168:169], v[168:169], 0, v[164:165]
	v_ashrrev_i32_e32 v147, 31, v146
	v_lshl_add_u64 v[168:169], v[146:147], 2, v[168:169]
	v_add_co_u32_e32 v168, vcc, 0x100000, v168
	s_nop 1
	v_addc_co_u32_e32 v169, vcc, 0, v169, vcc
	global_store_dwordx4 v[168:169], v[62:65], off

.LBB0_3922:
	v_bfe_u32 v138, v58, 16, 1
	v_add3_u32 v138, v58, v138, s78
	v_bfe_u32 v147, v59, 16, 1
	v_lshrrev_b32_e32 v138, 16, v138
	v_add3_u32 v147, v59, v147, s78
	v_and_or_b32 v168, v147, s79, v138
	v_bfe_u32 v138, v60, 16, 1
	v_add3_u32 v138, v60, v138, s78
	v_bfe_u32 v147, v61, 16, 1
	v_lshrrev_b32_e32 v138, 16, v138
	v_add3_u32 v147, v61, v147, s78
	v_and_or_b32 v169, v147, s79, v138
	s_cmp_lt_i32 s10, 3
	s_cbranch_scc1 .LBB0_3930
	s_cmp_lg_u32 s10, 3
	s_cbranch_scc0 .LBB0_3927
	v_lshlrev_b32_e32 v184, 1, v178
	v_lshl_add_u64 v[182:183], s[50:51], 0, v[160:161]
	v_ashrrev_i32_e32 v185, 31, v184
	v_lshl_add_u64 v[182:183], v[182:183], 0, v[184:185]
	global_store_dwordx2 v[182:183], v[168:169], off
	s_and_saveexec_b64 s[68:69], s[8:9]
	s_cbranch_execz .LBB0_3926
	v_ashrrev_i32_e32 v163, 31, v162
	v_lshlrev_b64 v[182:183], 19, v[162:163]
	v_lshl_add_u64 v[182:183], s[52:53], 0, v[182:183]
	v_lshl_add_u64 v[182:183], v[182:183], 0, v[164:165]
	v_ashrrev_i32_e32 v147, 31, v146
	v_lshl_add_u64 v[182:183], v[146:147], 2, v[182:183]
	v_add_co_u32_e32 v182, vcc, 0x100000, v182
	s_nop 1
	v_addc_co_u32_e32 v183, vcc, 0, v183, vcc
	global_store_dwordx4 v[182:183], v[58:61], off offset:64

.LBB0_3934:
	v_bfe_u32 v138, v42, 16, 1
	v_add3_u32 v138, v42, v138, s78
	v_bfe_u32 v147, v43, 16, 1
	v_lshrrev_b32_e32 v138, 16, v138
	v_add3_u32 v147, v43, v147, s78
	v_and_or_b32 v168, v147, s79, v138
	v_bfe_u32 v138, v44, 16, 1
	v_add3_u32 v138, v44, v138, s78
	v_bfe_u32 v147, v45, 16, 1
	v_lshrrev_b32_e32 v138, 16, v138
	v_add3_u32 v147, v45, v147, s78
	v_and_or_b32 v169, v147, s79, v138
	s_cmp_lt_i32 s10, 3
	s_cbranch_scc1 .LBB0_3942
	s_cmp_lg_u32 s10, 3
	s_cbranch_scc0 .LBB0_3939
	v_lshlrev_b32_e32 v184, 1, v180
	v_lshl_add_u64 v[182:183], s[50:51], 0, v[160:161]
	v_ashrrev_i32_e32 v185, 31, v184
	v_lshl_add_u64 v[182:183], v[182:183], 0, v[184:185]
	global_store_dwordx2 v[182:183], v[168:169], off
	s_and_saveexec_b64 s[68:69], s[8:9]
	s_cbranch_execz .LBB0_3938
	v_ashrrev_i32_e32 v163, 31, v162
	v_lshlrev_b64 v[182:183], 19, v[162:163]
	v_lshl_add_u64 v[182:183], s[52:53], 0, v[182:183]
	v_lshl_add_u64 v[182:183], v[182:183], 0, v[164:165]
	v_ashrrev_i32_e32 v147, 31, v146
	v_lshl_add_u64 v[182:183], v[146:147], 2, v[182:183]
	v_add_co_u32_e32 v182, vcc, 0x100000, v182
	s_nop 1
	v_addc_co_u32_e32 v183, vcc, 0, v183, vcc
	global_store_dwordx4 v[182:183], v[42:45], off offset:512

.LBB0_3946:
	v_bfe_u32 v138, v34, 16, 1
	v_add3_u32 v138, v34, v138, s78
	v_bfe_u32 v147, v35, 16, 1
	v_lshrrev_b32_e32 v138, 16, v138
	v_add3_u32 v147, v35, v147, s78
	v_and_or_b32 v168, v147, s79, v138
	v_bfe_u32 v138, v36, 16, 1
	v_add3_u32 v138, v36, v138, s78
	v_bfe_u32 v147, v37, 16, 1
	v_lshrrev_b32_e32 v138, 16, v138
	v_add3_u32 v147, v37, v147, s78
	v_and_or_b32 v169, v147, s79, v138
	s_cmp_lt_i32 s10, 3
	s_cbranch_scc1 .LBB0_3954
	s_cmp_lg_u32 s10, 3
	s_cbranch_scc0 .LBB0_3951
	v_lshlrev_b32_e32 v184, 1, v179
	v_lshl_add_u64 v[182:183], s[50:51], 0, v[160:161]
	v_ashrrev_i32_e32 v185, 31, v184
	v_lshl_add_u64 v[182:183], v[182:183], 0, v[184:185]
	global_store_dwordx2 v[182:183], v[168:169], off
	s_and_saveexec_b64 s[68:69], s[8:9]
	s_cbranch_execz .LBB0_3950
	v_ashrrev_i32_e32 v163, 31, v162
	v_lshlrev_b64 v[162:163], 19, v[162:163]
	v_lshl_add_u64 v[162:163], s[52:53], 0, v[162:163]
	v_lshl_add_u64 v[162:163], v[162:163], 0, v[164:165]
	v_ashrrev_i32_e32 v147, 31, v146
	v_lshl_add_u64 v[162:163], v[146:147], 2, v[162:163]
	v_add_co_u32_e32 v162, vcc, 0x100000, v162
	s_nop 1
	v_addc_co_u32_e32 v163, vcc, 0, v163, vcc
	global_store_dwordx4 v[162:163], v[34:37], off offset:576

.LBB0_3957:
	s_and_b64 vcc, exec, s[68:69]
	v_lshl_add_u64 v[166:167], s[54:55], 0, v[158:159]
	s_cbranch_vccz .LBB0_3921
	v_pk_mul_f32 v[182:183], v[62:63], s[56:57] op_sel_hi:[1,0]
	v_pk_mul_f32 v[168:169], v[64:65], s[56:57] op_sel_hi:[1,0]
	v_bfe_u32 v138, v182, 16, 1
	v_add3_u32 v138, v182, v138, s78
	v_bfe_u32 v147, v183, 16, 1
	v_lshrrev_b32_e32 v138, 16, v138
	v_add3_u32 v147, v183, v147, s78
	v_and_or_b32 v182, v147, s79, v138
	v_bfe_u32 v138, v168, 16, 1
	v_add3_u32 v138, v168, v138, s78
	v_bfe_u32 v147, v169, 16, 1
	v_lshrrev_b32_e32 v138, 16, v138
	v_add3_u32 v147, v169, v147, s78
	v_and_or_b32 v183, v147, s79, v138
	v_lshl_add_u64 v[168:169], v[148:149], 1, v[166:167]
	global_store_dwordx2 v[168:169], v[182:183], off
	s_and_b64 vcc, exec, s[6:7]
	s_mov_b64 s[68:69], -1
	s_cbranch_vccz .LBB0_3922
.LBB0_3959:
	s_and_b64 vcc, exec, s[68:69]
	s_cbranch_vccz .LBB0_3933
	v_pk_mul_f32 v[182:183], v[58:59], s[56:57] op_sel_hi:[1,0]
	v_pk_mul_f32 v[168:169], v[60:61], s[56:57] op_sel_hi:[1,0]
	v_bfe_u32 v138, v182, 16, 1
	v_add3_u32 v138, v182, v138, s78
	v_bfe_u32 v147, v183, 16, 1
	v_lshrrev_b32_e32 v138, 16, v138
	v_add3_u32 v147, v183, v147, s78
	v_and_or_b32 v182, v147, s79, v138
	v_bfe_u32 v138, v168, 16, 1
	v_add3_u32 v138, v168, v138, s78
	v_bfe_u32 v147, v169, 16, 1
	v_lshrrev_b32_e32 v138, 16, v138
	v_add3_u32 v147, v169, v147, s78
	v_and_or_b32 v183, v147, s79, v138
	v_lshl_add_u64 v[168:169], v[150:151], 1, v[166:167]
	global_store_dwordx2 v[168:169], v[182:183], off
	s_and_b64 vcc, exec, s[6:7]
	s_mov_b64 s[68:69], -1
	s_cbranch_vccz .LBB0_3934
.LBB0_3961:
	s_and_b64 vcc, exec, s[68:69]
	s_cbranch_vccz .LBB0_3945
	v_pk_mul_f32 v[182:183], v[42:43], s[56:57] op_sel_hi:[1,0]
	v_pk_mul_f32 v[168:169], v[44:45], s[56:57] op_sel_hi:[1,0]
	v_bfe_u32 v138, v182, 16, 1
	v_add3_u32 v138, v182, v138, s78
	v_bfe_u32 v147, v183, 16, 1
	v_lshrrev_b32_e32 v138, 16, v138
	v_add3_u32 v147, v183, v147, s78
	v_and_or_b32 v182, v147, s79, v138
	v_bfe_u32 v138, v168, 16, 1
	v_add3_u32 v138, v168, v138, s78
	v_bfe_u32 v147, v169, 16, 1
	v_lshrrev_b32_e32 v138, 16, v138
	v_add3_u32 v147, v169, v147, s78
	v_and_or_b32 v183, v147, s79, v138
	v_lshl_add_u64 v[168:169], v[152:153], 1, v[166:167]
	global_store_dwordx2 v[168:169], v[182:183], off
	s_and_b64 vcc, exec, s[6:7]
	s_mov_b64 s[68:69], -1
	s_cbranch_vccz .LBB0_3946
.LBB0_3963:
	s_and_b64 vcc, exec, s[68:69]
	s_cbranch_vccz .LBB0_3965
	v_pk_mul_f32 v[160:161], v[34:35], s[56:57] op_sel_hi:[1,0]
	v_pk_mul_f32 v[158:159], v[36:37], s[56:57] op_sel_hi:[1,0]
	v_bfe_u32 v138, v160, 16, 1
	v_add3_u32 v138, v160, v138, s78
	v_bfe_u32 v147, v161, 16, 1
	v_lshrrev_b32_e32 v138, 16, v138
	v_add3_u32 v147, v161, v147, s78
	v_and_or_b32 v160, v147, s79, v138
	v_bfe_u32 v138, v158, 16, 1
	v_add3_u32 v138, v158, v138, s78
	v_bfe_u32 v147, v159, 16, 1
	v_lshrrev_b32_e32 v138, 16, v138
	v_add3_u32 v147, v159, v147, s78
	v_and_or_b32 v161, v147, s79, v138
	v_lshl_add_u64 v[158:159], v[156:157], 1, v[166:167]
	global_store_dwordx2 v[158:159], v[160:161], off
.LBB0_3965:
	v_add_u32_e32 v162, 0x90, v154
	v_ashrrev_i32_e32 v138, 10, v162
	v_and_b32_e32 v181, -2, v138
	v_lshrrev_b32_e32 v138, 3, v162
	v_and_b32_e32 v155, 0xfe, v138
	v_and_b32_e32 v138, 0x1fff, v162
	v_ashrrev_i32_e32 v163, 31, v162
	v_cmp_lt_u32_e64 s[8:9], s77, v138
	v_add_u32_e32 v138, 0xffffe200, v138
	v_lshlrev_b64 v[160:161], 9, v[162:163]
	v_lshlrev_b64 v[158:159], 10, v[162:163]
	v_ashrrev_i32_e32 v162, 13, v162
	v_lshlrev_b64 v[164:165], 10, v[138:139]
	s_and_b64 vcc, exec, s[6:7]
	s_mov_b64 s[68:69], -1
	s_cbranch_vccnz .LBB0_4013
	v_bfe_u32 v138, v54, 16, 1
	v_add3_u32 v138, v54, v138, s78
	v_bfe_u32 v147, v55, 16, 1
	v_lshrrev_b32_e32 v138, 16, v138
	v_add3_u32 v147, v55, v147, s78
	v_and_or_b32 v166, v147, s79, v138
	v_bfe_u32 v138, v56, 16, 1
	v_add3_u32 v138, v56, v138, s78
	v_bfe_u32 v147, v57, 16, 1
	v_lshrrev_b32_e32 v138, 16, v138
	v_add3_u32 v147, v57, v147, s78
	v_and_or_b32 v167, v147, s79, v138
	s_cmp_lt_i32 s10, 3
	s_cbranch_scc1 .LBB0_3974
	s_cmp_lg_u32 s10, 3
	s_cbranch_scc0 .LBB0_3971
	v_lshlrev_b32_e32 v182, 1, v146
	v_lshl_add_u64 v[168:169], s[50:51], 0, v[160:161]
	v_ashrrev_i32_e32 v183, 31, v182
	v_lshl_add_u64 v[168:169], v[168:169], 0, v[182:183]
	global_store_dwordx2 v[168:169], v[166:167], off
	s_and_saveexec_b64 s[68:69], s[8:9]
	s_cbranch_execz .LBB0_3970
	v_ashrrev_i32_e32 v163, 31, v162
	v_lshlrev_b64 v[168:169], 19, v[162:163]
	v_lshl_add_u64 v[168:169], s[52:53], 0, v[168:169]
	v_lshl_add_u64 v[168:169], v[168:169], 0, v[164:165]
	v_ashrrev_i32_e32 v147, 31, v146
	v_lshl_add_u64 v[168:169], v[146:147], 2, v[168:169]
	v_add_co_u32_e32 v168, vcc, 0x100000, v168
	s_nop 1
	v_addc_co_u32_e32 v169, vcc, 0, v169, vcc
	global_store_dwordx4 v[168:169], v[54:57], off

.LBB0_3978:
	v_bfe_u32 v138, v50, 16, 1
	v_add3_u32 v138, v50, v138, s78
	v_bfe_u32 v147, v51, 16, 1
	v_lshrrev_b32_e32 v138, 16, v138
	v_add3_u32 v147, v51, v147, s78
	v_and_or_b32 v168, v147, s79, v138
	v_bfe_u32 v138, v52, 16, 1
	v_add3_u32 v138, v52, v138, s78
	v_bfe_u32 v147, v53, 16, 1
	v_lshrrev_b32_e32 v138, 16, v138
	v_add3_u32 v147, v53, v147, s78
	v_and_or_b32 v169, v147, s79, v138
	s_cmp_lt_i32 s10, 3
	s_cbranch_scc1 .LBB0_3986
	s_cmp_lg_u32 s10, 3
	s_cbranch_scc0 .LBB0_3983
	v_lshlrev_b32_e32 v184, 1, v178
	v_lshl_add_u64 v[182:183], s[50:51], 0, v[160:161]
	v_ashrrev_i32_e32 v185, 31, v184
	v_lshl_add_u64 v[182:183], v[182:183], 0, v[184:185]
	global_store_dwordx2 v[182:183], v[168:169], off
	s_and_saveexec_b64 s[68:69], s[8:9]
	s_cbranch_execz .LBB0_3982
	v_ashrrev_i32_e32 v163, 31, v162
	v_lshlrev_b64 v[182:183], 19, v[162:163]
	v_lshl_add_u64 v[182:183], s[52:53], 0, v[182:183]
	v_lshl_add_u64 v[182:183], v[182:183], 0, v[164:165]
	v_ashrrev_i32_e32 v147, 31, v146
	v_lshl_add_u64 v[182:183], v[146:147], 2, v[182:183]
	v_add_co_u32_e32 v182, vcc, 0x100000, v182
	s_nop 1
	v_addc_co_u32_e32 v183, vcc, 0, v183, vcc
	global_store_dwordx4 v[182:183], v[50:53], off offset:64

.LBB0_3990:
	v_bfe_u32 v138, v26, 16, 1
	v_add3_u32 v138, v26, v138, s78
	v_bfe_u32 v147, v27, 16, 1
	v_lshrrev_b32_e32 v138, 16, v138
	v_add3_u32 v147, v27, v147, s78
	v_and_or_b32 v168, v147, s79, v138
	v_bfe_u32 v138, v28, 16, 1
	v_add3_u32 v138, v28, v138, s78
	v_bfe_u32 v147, v29, 16, 1
	v_lshrrev_b32_e32 v138, 16, v138
	v_add3_u32 v147, v29, v147, s78
	v_and_or_b32 v169, v147, s79, v138
	s_cmp_lt_i32 s10, 3
	s_cbranch_scc1 .LBB0_3998
	s_cmp_lg_u32 s10, 3
	s_cbranch_scc0 .LBB0_3995
	v_lshlrev_b32_e32 v184, 1, v180
	v_lshl_add_u64 v[182:183], s[50:51], 0, v[160:161]
	v_ashrrev_i32_e32 v185, 31, v184
	v_lshl_add_u64 v[182:183], v[182:183], 0, v[184:185]
	global_store_dwordx2 v[182:183], v[168:169], off
	s_and_saveexec_b64 s[68:69], s[8:9]
	s_cbranch_execz .LBB0_3994
	v_ashrrev_i32_e32 v163, 31, v162
	v_lshlrev_b64 v[182:183], 19, v[162:163]
	v_lshl_add_u64 v[182:183], s[52:53], 0, v[182:183]
	v_lshl_add_u64 v[182:183], v[182:183], 0, v[164:165]
	v_ashrrev_i32_e32 v147, 31, v146
	v_lshl_add_u64 v[182:183], v[146:147], 2, v[182:183]
	v_add_co_u32_e32 v182, vcc, 0x100000, v182
	s_nop 1
	v_addc_co_u32_e32 v183, vcc, 0, v183, vcc
	global_store_dwordx4 v[182:183], v[26:29], off offset:512

.LBB0_4002:
	v_bfe_u32 v138, v18, 16, 1
	v_add3_u32 v138, v18, v138, s78
	v_bfe_u32 v147, v19, 16, 1
	v_lshrrev_b32_e32 v138, 16, v138
	v_add3_u32 v147, v19, v147, s78
	v_and_or_b32 v168, v147, s79, v138
	v_bfe_u32 v138, v20, 16, 1
	v_add3_u32 v138, v20, v138, s78
	v_bfe_u32 v147, v21, 16, 1
	v_lshrrev_b32_e32 v138, 16, v138
	v_add3_u32 v147, v21, v147, s78
	v_and_or_b32 v169, v147, s79, v138
	s_cmp_lt_i32 s10, 3
	s_cbranch_scc1 .LBB0_4010
	s_cmp_lg_u32 s10, 3
	s_cbranch_scc0 .LBB0_4007
	v_lshlrev_b32_e32 v184, 1, v179
	v_lshl_add_u64 v[182:183], s[50:51], 0, v[160:161]
	v_ashrrev_i32_e32 v185, 31, v184
	v_lshl_add_u64 v[182:183], v[182:183], 0, v[184:185]
	global_store_dwordx2 v[182:183], v[168:169], off
	s_and_saveexec_b64 s[68:69], s[8:9]
	s_cbranch_execz .LBB0_4006
	v_ashrrev_i32_e32 v163, 31, v162
	v_lshlrev_b64 v[162:163], 19, v[162:163]
	v_lshl_add_u64 v[162:163], s[52:53], 0, v[162:163]
	v_lshl_add_u64 v[162:163], v[162:163], 0, v[164:165]
	v_ashrrev_i32_e32 v147, 31, v146
	v_lshl_add_u64 v[162:163], v[146:147], 2, v[162:163]
	v_add_co_u32_e32 v162, vcc, 0x100000, v162
	s_nop 1
	v_addc_co_u32_e32 v163, vcc, 0, v163, vcc
	global_store_dwordx4 v[162:163], v[18:21], off offset:576

.LBB0_4013:
	s_and_b64 vcc, exec, s[68:69]
	v_lshl_add_u64 v[166:167], s[54:55], 0, v[158:159]
	s_cbranch_vccz .LBB0_3977
	v_pk_mul_f32 v[182:183], v[54:55], s[56:57] op_sel_hi:[1,0]
	v_pk_mul_f32 v[168:169], v[56:57], s[56:57] op_sel_hi:[1,0]
	v_bfe_u32 v138, v182, 16, 1
	v_add3_u32 v138, v182, v138, s78
	v_bfe_u32 v147, v183, 16, 1
	v_lshrrev_b32_e32 v138, 16, v138
	v_add3_u32 v147, v183, v147, s78
	v_and_or_b32 v182, v147, s79, v138
	v_bfe_u32 v138, v168, 16, 1
	v_add3_u32 v138, v168, v138, s78
	v_bfe_u32 v147, v169, 16, 1
	v_lshrrev_b32_e32 v138, 16, v138
	v_add3_u32 v147, v169, v147, s78
	v_and_or_b32 v183, v147, s79, v138
	v_lshl_add_u64 v[168:169], v[148:149], 1, v[166:167]
	global_store_dwordx2 v[168:169], v[182:183], off
	s_and_b64 vcc, exec, s[6:7]
	s_mov_b64 s[68:69], -1
	s_cbranch_vccz .LBB0_3978
.LBB0_4015:
	s_and_b64 vcc, exec, s[68:69]
	s_cbranch_vccz .LBB0_3989
	v_pk_mul_f32 v[182:183], v[50:51], s[56:57] op_sel_hi:[1,0]
	v_pk_mul_f32 v[168:169], v[52:53], s[56:57] op_sel_hi:[1,0]
	v_bfe_u32 v138, v182, 16, 1
	v_add3_u32 v138, v182, v138, s78
	v_bfe_u32 v147, v183, 16, 1
	v_lshrrev_b32_e32 v138, 16, v138
	v_add3_u32 v147, v183, v147, s78
	v_and_or_b32 v182, v147, s79, v138
	v_bfe_u32 v138, v168, 16, 1
	v_add3_u32 v138, v168, v138, s78
	v_bfe_u32 v147, v169, 16, 1
	v_lshrrev_b32_e32 v138, 16, v138
	v_add3_u32 v147, v169, v147, s78
	v_and_or_b32 v183, v147, s79, v138
	v_lshl_add_u64 v[168:169], v[150:151], 1, v[166:167]
	global_store_dwordx2 v[168:169], v[182:183], off
	s_and_b64 vcc, exec, s[6:7]
	s_mov_b64 s[68:69], -1
	s_cbranch_vccz .LBB0_3990
.LBB0_4017:
	s_and_b64 vcc, exec, s[68:69]
	s_cbranch_vccz .LBB0_4001
	v_pk_mul_f32 v[182:183], v[26:27], s[56:57] op_sel_hi:[1,0]
	v_pk_mul_f32 v[168:169], v[28:29], s[56:57] op_sel_hi:[1,0]
	v_bfe_u32 v138, v182, 16, 1
	v_add3_u32 v138, v182, v138, s78
	v_bfe_u32 v147, v183, 16, 1
	v_lshrrev_b32_e32 v138, 16, v138
	v_add3_u32 v147, v183, v147, s78
	v_and_or_b32 v182, v147, s79, v138
	v_bfe_u32 v138, v168, 16, 1
	v_add3_u32 v138, v168, v138, s78
	v_bfe_u32 v147, v169, 16, 1
	v_lshrrev_b32_e32 v138, 16, v138
	v_add3_u32 v147, v169, v147, s78
	v_and_or_b32 v183, v147, s79, v138
	v_lshl_add_u64 v[168:169], v[152:153], 1, v[166:167]
	global_store_dwordx2 v[168:169], v[182:183], off
	s_and_b64 vcc, exec, s[6:7]
	s_mov_b64 s[68:69], -1
	s_cbranch_vccz .LBB0_4002
.LBB0_4019:
	s_and_b64 vcc, exec, s[68:69]
	s_cbranch_vccz .LBB0_4021
	v_pk_mul_f32 v[160:161], v[18:19], s[56:57] op_sel_hi:[1,0]
	v_pk_mul_f32 v[158:159], v[20:21], s[56:57] op_sel_hi:[1,0]
	v_bfe_u32 v138, v160, 16, 1
	v_add3_u32 v138, v160, v138, s78
	v_bfe_u32 v147, v161, 16, 1
	v_lshrrev_b32_e32 v138, 16, v138
	v_add3_u32 v147, v161, v147, s78
	v_and_or_b32 v160, v147, s79, v138
	v_bfe_u32 v138, v158, 16, 1
	v_add3_u32 v138, v158, v138, s78
	v_bfe_u32 v147, v159, 16, 1
	v_lshrrev_b32_e32 v138, 16, v138
	v_add3_u32 v147, v159, v147, s78
	v_and_or_b32 v161, v147, s79, v138
	v_lshl_add_u64 v[158:159], v[156:157], 1, v[166:167]
	global_store_dwordx2 v[158:159], v[160:161], off
.LBB0_4021:
	v_add_u32_e32 v162, 0xa0, v154
	v_ashrrev_i32_e32 v138, 10, v162
	v_and_b32_e32 v181, -2, v138
	v_lshrrev_b32_e32 v138, 3, v162
	v_and_b32_e32 v155, 0xfe, v138
	v_and_b32_e32 v138, 0x1fff, v162
	v_ashrrev_i32_e32 v163, 31, v162
	v_cmp_lt_u32_e64 s[8:9], s77, v138
	v_add_u32_e32 v138, 0xffffe200, v138
	v_lshlrev_b64 v[160:161], 9, v[162:163]
	v_lshlrev_b64 v[158:159], 10, v[162:163]
	v_ashrrev_i32_e32 v162, 13, v162
	v_lshlrev_b64 v[164:165], 10, v[138:139]
	s_and_b64 vcc, exec, s[6:7]
	s_mov_b64 s[68:69], -1
	s_cbranch_vccnz .LBB0_4069
	v_bfe_u32 v138, v46, 16, 1
	v_add3_u32 v138, v46, v138, s78
	v_bfe_u32 v147, v47, 16, 1
	v_lshrrev_b32_e32 v138, 16, v138
	v_add3_u32 v147, v47, v147, s78
	v_and_or_b32 v166, v147, s79, v138
	v_bfe_u32 v138, v48, 16, 1
	v_add3_u32 v138, v48, v138, s78
	v_bfe_u32 v147, v49, 16, 1
	v_lshrrev_b32_e32 v138, 16, v138
	v_add3_u32 v147, v49, v147, s78
	v_and_or_b32 v167, v147, s79, v138
	s_cmp_lt_i32 s10, 3
	s_cbranch_scc1 .LBB0_4030
	s_cmp_lg_u32 s10, 3
	s_cbranch_scc0 .LBB0_4027
	v_lshlrev_b32_e32 v182, 1, v146
	v_lshl_add_u64 v[168:169], s[50:51], 0, v[160:161]
	v_ashrrev_i32_e32 v183, 31, v182
	v_lshl_add_u64 v[168:169], v[168:169], 0, v[182:183]
	global_store_dwordx2 v[168:169], v[166:167], off
	s_and_saveexec_b64 s[68:69], s[8:9]
	s_cbranch_execz .LBB0_4026
	v_ashrrev_i32_e32 v163, 31, v162
	v_lshlrev_b64 v[168:169], 19, v[162:163]
	v_lshl_add_u64 v[168:169], s[52:53], 0, v[168:169]
	v_lshl_add_u64 v[168:169], v[168:169], 0, v[164:165]
	v_ashrrev_i32_e32 v147, 31, v146
	v_lshl_add_u64 v[168:169], v[146:147], 2, v[168:169]
	v_add_co_u32_e32 v168, vcc, 0x100000, v168
	s_nop 1
	v_addc_co_u32_e32 v169, vcc, 0, v169, vcc
	global_store_dwordx4 v[168:169], v[46:49], off

.LBB0_4034:
	v_bfe_u32 v138, v38, 16, 1
	v_add3_u32 v138, v38, v138, s78
	v_bfe_u32 v147, v39, 16, 1
	v_lshrrev_b32_e32 v138, 16, v138
	v_add3_u32 v147, v39, v147, s78
	v_and_or_b32 v168, v147, s79, v138
	v_bfe_u32 v138, v40, 16, 1
	v_add3_u32 v138, v40, v138, s78
	v_bfe_u32 v147, v41, 16, 1
	v_lshrrev_b32_e32 v138, 16, v138
	v_add3_u32 v147, v41, v147, s78
	v_and_or_b32 v169, v147, s79, v138
	s_cmp_lt_i32 s10, 3
	s_cbranch_scc1 .LBB0_4042
	s_cmp_lg_u32 s10, 3
	s_cbranch_scc0 .LBB0_4039
	v_lshlrev_b32_e32 v184, 1, v178
	v_lshl_add_u64 v[182:183], s[50:51], 0, v[160:161]
	v_ashrrev_i32_e32 v185, 31, v184
	v_lshl_add_u64 v[182:183], v[182:183], 0, v[184:185]
	global_store_dwordx2 v[182:183], v[168:169], off
	s_and_saveexec_b64 s[68:69], s[8:9]
	s_cbranch_execz .LBB0_4038
	v_ashrrev_i32_e32 v163, 31, v162
	v_lshlrev_b64 v[182:183], 19, v[162:163]
	v_lshl_add_u64 v[182:183], s[52:53], 0, v[182:183]
	v_lshl_add_u64 v[182:183], v[182:183], 0, v[164:165]
	v_ashrrev_i32_e32 v147, 31, v146
	v_lshl_add_u64 v[182:183], v[146:147], 2, v[182:183]
	v_add_co_u32_e32 v182, vcc, 0x100000, v182
	s_nop 1
	v_addc_co_u32_e32 v183, vcc, 0, v183, vcc
	global_store_dwordx4 v[182:183], v[38:41], off offset:64

.LBB0_4046:
	v_bfe_u32 v138, v14, 16, 1
	v_add3_u32 v138, v14, v138, s78
	v_bfe_u32 v147, v15, 16, 1
	v_lshrrev_b32_e32 v138, 16, v138
	v_add3_u32 v147, v15, v147, s78
	v_and_or_b32 v168, v147, s79, v138
	v_bfe_u32 v138, v16, 16, 1
	v_add3_u32 v138, v16, v138, s78
	v_bfe_u32 v147, v17, 16, 1
	v_lshrrev_b32_e32 v138, 16, v138
	v_add3_u32 v147, v17, v147, s78
	v_and_or_b32 v169, v147, s79, v138
	s_cmp_lt_i32 s10, 3
	s_cbranch_scc1 .LBB0_4054
	s_cmp_lg_u32 s10, 3
	s_cbranch_scc0 .LBB0_4051
	v_lshlrev_b32_e32 v184, 1, v180
	v_lshl_add_u64 v[182:183], s[50:51], 0, v[160:161]
	v_ashrrev_i32_e32 v185, 31, v184
	v_lshl_add_u64 v[182:183], v[182:183], 0, v[184:185]
	global_store_dwordx2 v[182:183], v[168:169], off
	s_and_saveexec_b64 s[68:69], s[8:9]
	s_cbranch_execz .LBB0_4050
	v_ashrrev_i32_e32 v163, 31, v162
	v_lshlrev_b64 v[182:183], 19, v[162:163]
	v_lshl_add_u64 v[182:183], s[52:53], 0, v[182:183]
	v_lshl_add_u64 v[182:183], v[182:183], 0, v[164:165]
	v_ashrrev_i32_e32 v147, 31, v146
	v_lshl_add_u64 v[182:183], v[146:147], 2, v[182:183]
	v_add_co_u32_e32 v182, vcc, 0x100000, v182
	s_nop 1
	v_addc_co_u32_e32 v183, vcc, 0, v183, vcc
	global_store_dwordx4 v[182:183], v[14:17], off offset:512

.LBB0_4058:
	v_bfe_u32 v138, v10, 16, 1
	v_add3_u32 v138, v10, v138, s78
	v_bfe_u32 v147, v11, 16, 1
	v_lshrrev_b32_e32 v138, 16, v138
	v_add3_u32 v147, v11, v147, s78
	v_and_or_b32 v168, v147, s79, v138
	v_bfe_u32 v138, v12, 16, 1
	v_add3_u32 v138, v12, v138, s78
	v_bfe_u32 v147, v13, 16, 1
	v_lshrrev_b32_e32 v138, 16, v138
	v_add3_u32 v147, v13, v147, s78
	v_and_or_b32 v169, v147, s79, v138
	s_cmp_lt_i32 s10, 3
	s_cbranch_scc1 .LBB0_4066
	s_cmp_lg_u32 s10, 3
	s_cbranch_scc0 .LBB0_4063
	v_lshlrev_b32_e32 v184, 1, v179
	v_lshl_add_u64 v[182:183], s[50:51], 0, v[160:161]
	v_ashrrev_i32_e32 v185, 31, v184
	v_lshl_add_u64 v[182:183], v[182:183], 0, v[184:185]
	global_store_dwordx2 v[182:183], v[168:169], off
	s_and_saveexec_b64 s[68:69], s[8:9]
	s_cbranch_execz .LBB0_4062
	v_ashrrev_i32_e32 v163, 31, v162
	v_lshlrev_b64 v[162:163], 19, v[162:163]
	v_lshl_add_u64 v[162:163], s[52:53], 0, v[162:163]
	v_lshl_add_u64 v[162:163], v[162:163], 0, v[164:165]
	v_ashrrev_i32_e32 v147, 31, v146
	v_lshl_add_u64 v[162:163], v[146:147], 2, v[162:163]
	v_add_co_u32_e32 v162, vcc, 0x100000, v162
	s_nop 1
	v_addc_co_u32_e32 v163, vcc, 0, v163, vcc
	global_store_dwordx4 v[162:163], v[10:13], off offset:576

.LBB0_4069:
	s_and_b64 vcc, exec, s[68:69]
	v_lshl_add_u64 v[166:167], s[54:55], 0, v[158:159]
	s_cbranch_vccz .LBB0_4033
	v_pk_mul_f32 v[182:183], v[46:47], s[56:57] op_sel_hi:[1,0]
	v_pk_mul_f32 v[168:169], v[48:49], s[56:57] op_sel_hi:[1,0]
	v_bfe_u32 v138, v182, 16, 1
	v_add3_u32 v138, v182, v138, s78
	v_bfe_u32 v147, v183, 16, 1
	v_lshrrev_b32_e32 v138, 16, v138
	v_add3_u32 v147, v183, v147, s78
	v_and_or_b32 v182, v147, s79, v138
	v_bfe_u32 v138, v168, 16, 1
	v_add3_u32 v138, v168, v138, s78
	v_bfe_u32 v147, v169, 16, 1
	v_lshrrev_b32_e32 v138, 16, v138
	v_add3_u32 v147, v169, v147, s78
	v_and_or_b32 v183, v147, s79, v138
	v_lshl_add_u64 v[168:169], v[148:149], 1, v[166:167]
	global_store_dwordx2 v[168:169], v[182:183], off
	s_and_b64 vcc, exec, s[6:7]
	s_mov_b64 s[68:69], -1
	s_cbranch_vccz .LBB0_4034
.LBB0_4071:
	s_and_b64 vcc, exec, s[68:69]
	s_cbranch_vccz .LBB0_4045
	v_pk_mul_f32 v[182:183], v[38:39], s[56:57] op_sel_hi:[1,0]
	v_pk_mul_f32 v[168:169], v[40:41], s[56:57] op_sel_hi:[1,0]
	v_bfe_u32 v138, v182, 16, 1
	v_add3_u32 v138, v182, v138, s78
	v_bfe_u32 v147, v183, 16, 1
	v_lshrrev_b32_e32 v138, 16, v138
	v_add3_u32 v147, v183, v147, s78
	v_and_or_b32 v182, v147, s79, v138
	v_bfe_u32 v138, v168, 16, 1
	v_add3_u32 v138, v168, v138, s78
	v_bfe_u32 v147, v169, 16, 1
	v_lshrrev_b32_e32 v138, 16, v138
	v_add3_u32 v147, v169, v147, s78
	v_and_or_b32 v183, v147, s79, v138
	v_lshl_add_u64 v[168:169], v[150:151], 1, v[166:167]
	global_store_dwordx2 v[168:169], v[182:183], off
	s_and_b64 vcc, exec, s[6:7]
	s_mov_b64 s[68:69], -1
	s_cbranch_vccz .LBB0_4046
.LBB0_4073:
	s_and_b64 vcc, exec, s[68:69]
	s_cbranch_vccz .LBB0_4057
	v_pk_mul_f32 v[182:183], v[14:15], s[56:57] op_sel_hi:[1,0]
	v_pk_mul_f32 v[168:169], v[16:17], s[56:57] op_sel_hi:[1,0]
	v_bfe_u32 v138, v182, 16, 1
	v_add3_u32 v138, v182, v138, s78
	v_bfe_u32 v147, v183, 16, 1
	v_lshrrev_b32_e32 v138, 16, v138
	v_add3_u32 v147, v183, v147, s78
	v_and_or_b32 v182, v147, s79, v138
	v_bfe_u32 v138, v168, 16, 1
	v_add3_u32 v138, v168, v138, s78
	v_bfe_u32 v147, v169, 16, 1
	v_lshrrev_b32_e32 v138, 16, v138
	v_add3_u32 v147, v169, v147, s78
	v_and_or_b32 v183, v147, s79, v138
	v_lshl_add_u64 v[168:169], v[152:153], 1, v[166:167]
	global_store_dwordx2 v[168:169], v[182:183], off
	s_and_b64 vcc, exec, s[6:7]
	s_mov_b64 s[68:69], -1
	s_cbranch_vccz .LBB0_4058
.LBB0_4075:
	s_and_b64 vcc, exec, s[68:69]
	s_cbranch_vccz .LBB0_4077
	v_pk_mul_f32 v[160:161], v[10:11], s[56:57] op_sel_hi:[1,0]
	v_pk_mul_f32 v[158:159], v[12:13], s[56:57] op_sel_hi:[1,0]
	v_bfe_u32 v138, v160, 16, 1
	v_add3_u32 v138, v160, v138, s78
	v_bfe_u32 v147, v161, 16, 1
	v_lshrrev_b32_e32 v138, 16, v138
	v_add3_u32 v147, v161, v147, s78
	v_and_or_b32 v160, v147, s79, v138
	v_bfe_u32 v138, v158, 16, 1
	v_add3_u32 v138, v158, v138, s78
	v_bfe_u32 v147, v159, 16, 1
	v_lshrrev_b32_e32 v138, 16, v138
	v_add3_u32 v147, v159, v147, s78
	v_and_or_b32 v161, v147, s79, v138
	v_lshl_add_u64 v[158:159], v[156:157], 1, v[166:167]
	global_store_dwordx2 v[158:159], v[160:161], off
.LBB0_4077:
	v_add_u32_e32 v160, 0xb0, v154
	v_ashrrev_i32_e32 v138, 10, v160
	v_and_b32_e32 v169, -2, v138
	v_lshrrev_b32_e32 v138, 3, v160
	v_and_b32_e32 v168, 0xfe, v138
	v_and_b32_e32 v138, 0x1fff, v160
	v_ashrrev_i32_e32 v161, 31, v160
	v_cmp_lt_u32_e64 s[8:9], s77, v138
	v_add_u32_e32 v138, 0xffffe200, v138
	v_lshlrev_b64 v[158:159], 9, v[160:161]
	v_lshlrev_b64 v[154:155], 10, v[160:161]
	v_ashrrev_i32_e32 v160, 13, v160
	v_lshlrev_b64 v[162:163], 10, v[138:139]
	s_and_b64 vcc, exec, s[6:7]
	s_mov_b64 s[68:69], -1
	s_cbranch_vccnz .LBB0_4125
	v_bfe_u32 v138, v30, 16, 1
	v_add3_u32 v138, v30, v138, s78
	v_bfe_u32 v147, v31, 16, 1
	v_lshrrev_b32_e32 v138, 16, v138
	v_add3_u32 v147, v31, v147, s78
	v_and_or_b32 v164, v147, s79, v138
	v_bfe_u32 v138, v32, 16, 1
	v_add3_u32 v138, v32, v138, s78
	v_bfe_u32 v147, v33, 16, 1
	v_lshrrev_b32_e32 v138, 16, v138
	v_add3_u32 v147, v33, v147, s78
	v_and_or_b32 v165, v147, s79, v138
	s_cmp_lt_i32 s10, 3
	s_cbranch_scc1 .LBB0_4086
	v_lshlrev_b32_e32 v166, 1, v146
	s_cmp_lg_u32 s10, 3
	v_ashrrev_i32_e32 v167, 31, v166
	s_cbranch_scc0 .LBB0_4083
	v_lshl_add_u64 v[182:183], s[50:51], 0, v[158:159]
	v_lshl_add_u64 v[182:183], v[182:183], 0, v[166:167]
	global_store_dwordx2 v[182:183], v[164:165], off
	s_and_saveexec_b64 s[68:69], s[8:9]
	s_cbranch_execz .LBB0_4082
	v_ashrrev_i32_e32 v161, 31, v160
	v_lshlrev_b64 v[182:183], 19, v[160:161]
	v_lshl_add_u64 v[182:183], s[52:53], 0, v[182:183]
	v_lshl_add_u64 v[182:183], v[182:183], 0, v[162:163]
	v_ashrrev_i32_e32 v147, 31, v146
	v_lshl_add_u64 v[182:183], v[146:147], 2, v[182:183]
	v_add_co_u32_e32 v182, vcc, 0x100000, v182
	s_nop 1
	v_addc_co_u32_e32 v183, vcc, 0, v183, vcc
	global_store_dwordx4 v[182:183], v[30:33], off

.LBB0_4090:
	v_bfe_u32 v138, v22, 16, 1
	v_add3_u32 v138, v22, v138, s78
	v_bfe_u32 v147, v23, 16, 1
	v_lshrrev_b32_e32 v138, 16, v138
	v_add3_u32 v147, v23, v147, s78
	v_and_or_b32 v148, v147, s79, v138
	v_bfe_u32 v138, v24, 16, 1
	v_add3_u32 v138, v24, v138, s78
	v_bfe_u32 v147, v25, 16, 1
	v_lshrrev_b32_e32 v138, 16, v138
	v_add3_u32 v147, v25, v147, s78
	v_and_or_b32 v149, v147, s79, v138
	s_cmp_lt_i32 s10, 3
	s_cbranch_scc1 .LBB0_4098
	v_lshlrev_b32_e32 v166, 1, v178
	s_cmp_lg_u32 s10, 3
	v_ashrrev_i32_e32 v167, 31, v166
	s_cbranch_scc0 .LBB0_4095
	v_lshl_add_u64 v[182:183], s[50:51], 0, v[158:159]
	v_lshl_add_u64 v[182:183], v[182:183], 0, v[166:167]
	global_store_dwordx2 v[182:183], v[148:149], off
	s_and_saveexec_b64 s[68:69], s[8:9]
	s_cbranch_execz .LBB0_4094
	v_ashrrev_i32_e32 v161, 31, v160
	v_lshlrev_b64 v[182:183], 19, v[160:161]
	v_lshl_add_u64 v[182:183], s[52:53], 0, v[182:183]
	v_lshl_add_u64 v[182:183], v[182:183], 0, v[162:163]
	v_ashrrev_i32_e32 v147, 31, v146
	v_lshl_add_u64 v[182:183], v[146:147], 2, v[182:183]
	v_add_co_u32_e32 v182, vcc, 0x100000, v182
	s_nop 1
	v_addc_co_u32_e32 v183, vcc, 0, v183, vcc
	global_store_dwordx4 v[182:183], v[22:25], off offset:64

.LBB0_4102:
	v_bfe_u32 v138, v6, 16, 1
	v_add3_u32 v138, v6, v138, s78
	v_bfe_u32 v147, v7, 16, 1
	v_lshrrev_b32_e32 v138, 16, v138
	v_add3_u32 v147, v7, v147, s78
	v_and_or_b32 v148, v147, s79, v138
	v_bfe_u32 v138, v8, 16, 1
	v_add3_u32 v138, v8, v138, s78
	v_bfe_u32 v147, v9, 16, 1
	v_lshrrev_b32_e32 v138, 16, v138
	v_add3_u32 v147, v9, v147, s78
	v_and_or_b32 v149, v147, s79, v138
	s_cmp_lt_i32 s10, 3
	s_cbranch_scc1 .LBB0_4110
	v_lshlrev_b32_e32 v150, 1, v180
	s_cmp_lg_u32 s10, 3
	v_ashrrev_i32_e32 v151, 31, v150
	s_cbranch_scc0 .LBB0_4107
	v_lshl_add_u64 v[166:167], s[50:51], 0, v[158:159]
	v_lshl_add_u64 v[166:167], v[166:167], 0, v[150:151]
	global_store_dwordx2 v[166:167], v[148:149], off
	s_and_saveexec_b64 s[68:69], s[8:9]
	s_cbranch_execz .LBB0_4106
	v_ashrrev_i32_e32 v161, 31, v160
	v_lshlrev_b64 v[166:167], 19, v[160:161]
	v_lshl_add_u64 v[166:167], s[52:53], 0, v[166:167]
	v_lshl_add_u64 v[166:167], v[166:167], 0, v[162:163]
	v_ashrrev_i32_e32 v147, 31, v146
	v_lshl_add_u64 v[166:167], v[146:147], 2, v[166:167]
	v_add_co_u32_e32 v166, vcc, 0x100000, v166
	s_nop 1
	v_addc_co_u32_e32 v167, vcc, 0, v167, vcc
	global_store_dwordx4 v[166:167], v[6:9], off offset:512

.LBB0_4114:
	v_bfe_u32 v138, v2, 16, 1
	v_add3_u32 v138, v2, v138, s78
	v_bfe_u32 v147, v3, 16, 1
	v_lshrrev_b32_e32 v138, 16, v138
	v_add3_u32 v147, v3, v147, s78
	v_and_or_b32 v148, v147, s79, v138
	v_bfe_u32 v138, v4, 16, 1
	v_add3_u32 v138, v4, v138, s78
	v_bfe_u32 v147, v5, 16, 1
	v_lshrrev_b32_e32 v138, 16, v138
	v_add3_u32 v147, v5, v147, s78
	v_and_or_b32 v149, v147, s79, v138
	s_cmp_lt_i32 s10, 3
	s_cbranch_scc1 .LBB0_4122
	v_lshlrev_b32_e32 v150, 1, v179
	s_cmp_lg_u32 s10, 3
	v_ashrrev_i32_e32 v151, 31, v150
	s_cbranch_scc0 .LBB0_4119
	v_lshl_add_u64 v[152:153], s[50:51], 0, v[158:159]
	v_lshl_add_u64 v[152:153], v[152:153], 0, v[150:151]
	global_store_dwordx2 v[152:153], v[148:149], off
	s_and_saveexec_b64 s[6:7], s[8:9]
	s_cbranch_execz .LBB0_4118
	v_ashrrev_i32_e32 v161, 31, v160
	v_lshlrev_b64 v[152:153], 19, v[160:161]
	v_lshl_add_u64 v[152:153], s[52:53], 0, v[152:153]
	v_lshl_add_u64 v[152:153], v[152:153], 0, v[162:163]
	v_ashrrev_i32_e32 v147, 31, v146
	v_lshl_add_u64 v[152:153], v[146:147], 2, v[152:153]
	v_add_co_u32_e32 v152, vcc, 0x100000, v152
	s_nop 1
	v_addc_co_u32_e32 v153, vcc, 0, v153, vcc
	global_store_dwordx4 v[152:153], v[2:5], off offset:576

.LBB0_4125:
	s_and_b64 vcc, exec, s[68:69]
	v_lshl_add_u64 v[164:165], s[54:55], 0, v[154:155]
	s_cbranch_vccz .LBB0_4089
	v_pk_mul_f32 v[182:183], v[30:31], s[56:57] op_sel_hi:[1,0]
	v_pk_mul_f32 v[166:167], v[32:33], s[56:57] op_sel_hi:[1,0]
	v_bfe_u32 v138, v182, 16, 1
	v_add3_u32 v138, v182, v138, s78
	v_bfe_u32 v147, v183, 16, 1
	v_lshrrev_b32_e32 v138, 16, v138
	v_add3_u32 v147, v183, v147, s78
	v_and_or_b32 v182, v147, s79, v138
	v_bfe_u32 v138, v166, 16, 1
	v_add3_u32 v138, v166, v138, s78
	v_bfe_u32 v147, v167, 16, 1
	v_lshrrev_b32_e32 v138, 16, v138
	v_add3_u32 v147, v167, v147, s78
	v_and_or_b32 v183, v147, s79, v138
	v_lshl_add_u64 v[148:149], v[148:149], 1, v[164:165]
	global_store_dwordx2 v[148:149], v[182:183], off
	s_and_b64 vcc, exec, s[6:7]
	s_mov_b64 s[68:69], -1
	s_cbranch_vccz .LBB0_4090
.LBB0_4127:
	s_and_b64 vcc, exec, s[68:69]
	s_cbranch_vccz .LBB0_4101
	v_pk_mul_f32 v[166:167], v[22:23], s[56:57] op_sel_hi:[1,0]
	v_pk_mul_f32 v[148:149], v[24:25], s[56:57] op_sel_hi:[1,0]
	v_bfe_u32 v138, v166, 16, 1
	v_add3_u32 v138, v166, v138, s78
	v_bfe_u32 v147, v167, 16, 1
	v_lshrrev_b32_e32 v138, 16, v138
	v_add3_u32 v147, v167, v147, s78
	v_and_or_b32 v166, v147, s79, v138
	v_bfe_u32 v138, v148, 16, 1
	v_add3_u32 v138, v148, v138, s78
	v_bfe_u32 v147, v149, 16, 1
	v_lshrrev_b32_e32 v138, 16, v138
	v_add3_u32 v147, v149, v147, s78
	v_and_or_b32 v167, v147, s79, v138
	v_lshl_add_u64 v[148:149], v[150:151], 1, v[164:165]
	global_store_dwordx2 v[148:149], v[166:167], off
	s_and_b64 vcc, exec, s[6:7]
	s_mov_b64 s[68:69], -1
	s_cbranch_vccz .LBB0_4102
.LBB0_4129:
	s_and_b64 vcc, exec, s[68:69]
	s_cbranch_vccz .LBB0_4113
	v_pk_mul_f32 v[150:151], v[6:7], s[56:57] op_sel_hi:[1,0]
	v_pk_mul_f32 v[148:149], v[8:9], s[56:57] op_sel_hi:[1,0]
	v_bfe_u32 v138, v150, 16, 1
	v_add3_u32 v138, v150, v138, s78
	v_bfe_u32 v147, v151, 16, 1
	v_lshrrev_b32_e32 v138, 16, v138
	v_add3_u32 v147, v151, v147, s78
	v_and_or_b32 v150, v147, s79, v138
	v_bfe_u32 v138, v148, 16, 1
	v_add3_u32 v138, v148, v138, s78
	v_bfe_u32 v147, v149, 16, 1
	v_lshrrev_b32_e32 v138, 16, v138
	v_add3_u32 v147, v149, v147, s78
	v_and_or_b32 v151, v147, s79, v138
	v_lshl_add_u64 v[148:149], v[152:153], 1, v[164:165]
	global_store_dwordx2 v[148:149], v[150:151], off
	s_and_b64 vcc, exec, s[6:7]
	s_mov_b64 s[6:7], -1
	s_cbranch_vccz .LBB0_4114
.LBB0_4131:
	s_and_b64 vcc, exec, s[6:7]
	s_cbranch_vccz .LBB0_4133
	v_pk_mul_f32 v[148:149], v[2:3], s[56:57] op_sel_hi:[1,0]
	v_pk_mul_f32 v[146:147], v[4:5], s[56:57] op_sel_hi:[1,0]
	v_bfe_u32 v138, v148, 16, 1
	v_add3_u32 v138, v148, v138, s78
	v_bfe_u32 v145, v149, 16, 1
	v_lshrrev_b32_e32 v138, 16, v138
	v_add3_u32 v145, v149, v145, s78
	v_and_or_b32 v148, v145, s79, v138
	v_bfe_u32 v138, v146, 16, 1
	v_add3_u32 v138, v146, v138, s78
	v_bfe_u32 v145, v147, 16, 1
	v_lshrrev_b32_e32 v138, 16, v138
	v_add3_u32 v145, v147, v145, s78
	v_and_or_b32 v149, v145, s79, v138
	v_lshl_add_u64 v[146:147], v[156:157], 1, v[164:165]
	global_store_dwordx2 v[146:147], v[148:149], off

.LBB0_4194:
	s_nop 0
	v_lshl_add_u64 v[12:13], s[14:15], 0, v[2:3]
	v_add_co_u32_e32 v14, vcc, 0x16000000, v12
	v_lshl_add_u64 v[16:17], s[8:9], 0, v[2:3]
	s_nop 0
	v_addc_co_u32_e32 v15, vcc, 0, v13, vcc
	v_add_co_u32_e32 v12, vcc, 0x16001000, v12
	global_load_dwordx4 v[4:7], v[14:15], off offset:2048
	global_load_dwordx4 v[8:11], v[14:15], off offset:3072
	v_addc_co_u32_e32 v13, vcc, 0, v13, vcc
	global_load_dwordx4 v[12:15], v[12:13], off
	s_add_i32 s12, s12, s6
	s_add_u32 s8, s8, s10
	v_add_co_u32_e32 v18, vcc, 0x8320000, v16
	s_addc_u32 s9, s9, s11
	s_nop 0
	v_addc_co_u32_e32 v19, vcc, 0, v17, vcc
	s_add_u32 s14, s14, s2
	v_add_co_u32_e32 v20, vcc, 0x8360000, v16
	s_addc_u32 s15, s15, s3
	s_nop 0
	v_addc_co_u32_e32 v21, vcc, 0, v17, vcc
	v_add_co_u32_e32 v16, vcc, 0x83a0000, v16
	s_cmpk_lt_i32 s12, 0x80
	s_nop 0
	v_addc_co_u32_e32 v17, vcc, 0, v17, vcc
	s_waitcnt vmcnt(0) lgkmcnt(0)
	global_store_dwordx4 v[18:19], v[4:7], off
	global_store_dwordx4 v[20:21], v[8:11], off
	global_store_dwordx4 v[16:17], v[12:15], off
	s_cbranch_scc1 .LBB0_4194

.LBB0_4196:
	s_lshl_b32 s2, s19, 2
	v_add_u32_e32 v132, s45, v138
	s_add_u32 s6, s34, s2
	v_ashrrev_i32_e32 v133, 31, v132
	s_addc_u32 s7, s35, 0
	v_lshlrev_b64 v[132:133], 10, v[132:133]
	v_lshl_add_u64 v[132:133], s[6:7], 0, v[132:133]
	v_mov_b32_e32 v131, v179
	v_lshl_add_u64 v[132:133], v[132:133], 0, v[130:131]
	v_readlane_b32 s2, v228, 21
	global_store_dwordx4 v[132:133], v[126:129], off
	global_store_dwordx4 v[132:133], v[122:125], off offset:64
	global_store_dwordx4 v[132:133], v[110:113], off offset:512
	global_store_dwordx4 v[132:133], v[102:105], off offset:576
	s_nop 1
	v_add_u32_e32 v102, s2, v138
	v_ashrrev_i32_e32 v103, 31, v102
	v_lshlrev_b64 v[102:103], 10, v[102:103]
	v_lshl_add_u64 v[102:103], s[6:7], 0, v[102:103]
	v_lshl_add_u64 v[102:103], v[102:103], 0, v[130:131]
	global_store_dwordx4 v[102:103], v[118:121], off
	global_store_dwordx4 v[102:103], v[114:117], off offset:64
	global_store_dwordx4 v[102:103], v[94:97], off offset:512
	global_store_dwordx4 v[102:103], v[86:89], off offset:576
	s_nop 1
	v_add_u32_e32 v86, s3, v138
	v_ashrrev_i32_e32 v87, 31, v86
	v_lshlrev_b64 v[86:87], 10, v[86:87]
	v_lshl_add_u64 v[86:87], s[6:7], 0, v[86:87]
	v_lshl_add_u64 v[86:87], v[86:87], 0, v[130:131]
	global_store_dwordx4 v[86:87], v[106:109], off
	global_store_dwordx4 v[86:87], v[98:101], off offset:64
	global_store_dwordx4 v[86:87], v[78:81], off offset:512
	global_store_dwordx4 v[86:87], v[74:77], off offset:576
	s_nop 1
	v_add_u32_e32 v74, s42, v138
	v_ashrrev_i32_e32 v75, 31, v74
	v_lshlrev_b64 v[74:75], 10, v[74:75]
	v_lshl_add_u64 v[74:75], s[6:7], 0, v[74:75]
	v_lshl_add_u64 v[74:75], v[74:75], 0, v[130:131]
	global_store_dwordx4 v[74:75], v[90:93], off
	global_store_dwordx4 v[74:75], v[82:85], off offset:64
	global_store_dwordx4 v[74:75], v[70:73], off offset:512
	global_store_dwordx4 v[74:75], v[66:69], off offset:576
	s_nop 1
	v_add_u32_e32 v66, s43, v138
	v_ashrrev_i32_e32 v67, 31, v66
	v_lshlrev_b64 v[66:67], 10, v[66:67]
	v_lshl_add_u64 v[66:67], s[6:7], 0, v[66:67]
	v_lshl_add_u64 v[66:67], v[66:67], 0, v[130:131]
	global_store_dwordx4 v[66:67], v[62:65], off
	global_store_dwordx4 v[66:67], v[58:61], off offset:64
	global_store_dwordx4 v[66:67], v[46:49], off offset:512
	global_store_dwordx4 v[66:67], v[38:41], off offset:576
	s_nop 1
	v_add_u32_e32 v38, s49, v138
	v_ashrrev_i32_e32 v39, 31, v38
	v_lshlrev_b64 v[38:39], 10, v[38:39]
	v_lshl_add_u64 v[38:39], s[6:7], 0, v[38:39]
	v_lshl_add_u64 v[38:39], v[38:39], 0, v[130:131]
	global_store_dwordx4 v[38:39], v[54:57], off
	global_store_dwordx4 v[38:39], v[50:53], off offset:64
	global_store_dwordx4 v[38:39], v[30:33], off offset:512
	global_store_dwordx4 v[38:39], v[22:25], off offset:576
	s_nop 1
	v_add_u32_e32 v22, s52, v138
	v_ashrrev_i32_e32 v23, 31, v22
	v_lshlrev_b64 v[22:23], 10, v[22:23]
	v_lshl_add_u64 v[22:23], s[6:7], 0, v[22:23]
	v_lshl_add_u64 v[22:23], v[22:23], 0, v[130:131]
	global_store_dwordx4 v[22:23], v[42:45], off
	global_store_dwordx4 v[22:23], v[34:37], off offset:64
	global_store_dwordx4 v[22:23], v[14:17], off offset:512
	global_store_dwordx4 v[22:23], v[10:13], off offset:576
	s_nop 1
	v_add_u32_e32 v10, s53, v138
	v_ashrrev_i32_e32 v11, 31, v10
	v_lshlrev_b64 v[10:11], 10, v[10:11]
	v_lshl_add_u64 v[10:11], s[6:7], 0, v[10:11]
	v_lshl_add_u64 v[10:11], v[10:11], 0, v[130:131]
	global_store_dwordx4 v[10:11], v[26:29], off
	global_store_dwordx4 v[10:11], v[18:21], off offset:64
	global_store_dwordx4 v[10:11], v[6:9], off offset:512
	global_store_dwordx4 v[10:11], v[2:5], off offset:576
	s_waitcnt vmcnt(0)
	s_barrier

.LBB0_4198:
	v_mov_b32_e32 v180, v0
	s_mov_b64 s[6:7], -1
	v_readfirstlane_b32 s22, v180
	s_ashr_i32 s10, s22, 6
	v_and_b32_e32 v182, 63, v180
	s_cmp_eq_u32 s2, s33
	s_cbranch_scc1 .LBB0_4204
	s_waitcnt lgkmcnt(0)
	v_mov_b64_e32 v[2:3], s[0:1]
	global_load_dwordx2 v[4:5], v[2:3], off offset:64 sc0 sc1
	s_waitcnt vmcnt(0)
	global_load_dwordx2 v[8:9], v[2:3], off offset:32 sc0 sc1
	s_waitcnt vmcnt(0)
	v_ashrrev_i32_e32 v41, 5, v180
	v_lshlrev_b32_e32 v2, 14, v41
	v_and_b32_e32 v178, 0x1c000, v2
	s_mov_b32 s81, s57
	v_lshlrev_b32_e32 v40, 4, v180
	s_mov_b64 s[6:7], 0x14000000
	v_and_b32_e32 v6, 0xf0, v40
	v_mov_b32_e32 v7, v179
	s_lshl_b32 s2, s10, 5
	v_and_b32_e32 v203, 31, v180
	v_lshrrev_b32_e32 v181, 5, v182
	s_mov_b64 s[8:9], 0
	s_waitcnt lgkmcnt(0)
	v_lshl_add_u64 v[24:25], s[54:55], 2, v[4:5]
	v_lshl_add_u64 v[2:3], v[8:9], 0, v[178:179]
	v_lshl_add_u64 v[4:5], v[2:3], 0, s[80:81]
	v_and_b32_e32 v2, 0x100, v40
	v_mov_b32_e32 v3, v179
	v_lshl_add_u64 v[4:5], v[4:5], 0, v[2:3]
	v_lshl_add_u64 v[10:11], v[4:5], 0, s[6:7]
	v_ashrrev_i32_e32 v4, 8, v180
	v_ashrrev_i32_e32 v5, 31, v4
	v_lshl_add_u64 v[4:5], v[4:5], 2, v[24:25]
	global_load_dword v4, v[4:5], off
	v_add_u32_e32 v3, 16, v41
	s_and_b32 s6, s2, 0xffffffc0
	s_lshl_b32 s2, s10, 7
	s_and_b32 s11, s2, 0x80
	s_mov_b32 s2, 0x20000
	v_lshl_add_u64 v[8:9], v[8:9], 0, s[76:77]
	s_waitcnt vmcnt(0)
	v_ashrrev_i32_e32 v5, 31, v4
	v_lshlrev_b64 v[4:5], 17, v[4:5]
	v_lshl_add_u64 v[12:13], v[10:11], 0, v[4:5]
	v_lshl_add_u64 v[18:19], v[12:13], 0, v[6:7]
	v_ashrrev_i32_e32 v12, 3, v3
	v_ashrrev_i32_e32 v13, 31, v12
	v_lshl_add_u64 v[12:13], v[12:13], 2, v[24:25]
	global_load_dword v12, v[12:13], off
	v_add_u32_e32 v3, 32, v41
	v_or_b32_e32 v4, v4, v178
	v_or3_b32 v4, v4, v2, v6
	v_lshl_add_u64 v[200:201], v[8:9], 0, v[4:5]
	s_waitcnt vmcnt(0)
	v_ashrrev_i32_e32 v13, 31, v12
	v_lshlrev_b64 v[12:13], 17, v[12:13]
	v_lshl_add_u64 v[14:15], v[10:11], 0, v[12:13]
	v_lshl_add_u64 v[22:23], v[14:15], 0, v[6:7]
	v_ashrrev_i32_e32 v14, 3, v3
	v_ashrrev_i32_e32 v15, 31, v14
	v_lshl_add_u64 v[14:15], v[14:15], 2, v[24:25]
	global_load_dword v14, v[14:15], off
	v_add_u32_e32 v3, 48, v41
	v_or_b32_e32 v12, v12, v178
	v_or3_b32 v12, v12, v2, v6
	v_lshl_add_u64 v[198:199], v[8:9], 0, v[12:13]
	s_waitcnt vmcnt(0)
	v_ashrrev_i32_e32 v15, 31, v14
	v_lshlrev_b64 v[14:15], 17, v[14:15]
	v_lshl_add_u64 v[16:17], v[10:11], 0, v[14:15]
	v_lshl_add_u64 v[28:29], v[16:17], 0, v[6:7]
	v_ashrrev_i32_e32 v16, 3, v3
	v_ashrrev_i32_e32 v17, 31, v16
	v_lshl_add_u64 v[16:17], v[16:17], 2, v[24:25]
	global_load_dword v16, v[16:17], off
	v_add_u32_e32 v3, 64, v41
	v_or_b32_e32 v14, v14, v178
	v_or3_b32 v14, v14, v2, v6
	v_lshl_add_u64 v[196:197], v[8:9], 0, v[14:15]
	s_waitcnt vmcnt(0)
	v_ashrrev_i32_e32 v17, 31, v16
	v_lshlrev_b64 v[16:17], 17, v[16:17]
	v_lshl_add_u64 v[20:21], v[10:11], 0, v[16:17]
	v_lshl_add_u64 v[32:33], v[20:21], 0, v[6:7]
	v_ashrrev_i32_e32 v20, 3, v3
	v_ashrrev_i32_e32 v21, 31, v20
	v_lshl_add_u64 v[20:21], v[20:21], 2, v[24:25]
	global_load_dword v20, v[20:21], off
	v_add_u32_e32 v3, 0x50, v41
	v_or_b32_e32 v16, v16, v178
	v_or3_b32 v16, v16, v2, v6
	v_lshl_add_u64 v[194:195], v[8:9], 0, v[16:17]
	s_waitcnt vmcnt(0)
	v_ashrrev_i32_e32 v21, 31, v20
	v_lshlrev_b64 v[20:21], 17, v[20:21]
	v_lshl_add_u64 v[26:27], v[10:11], 0, v[20:21]
	v_lshl_add_u64 v[34:35], v[26:27], 0, v[6:7]
	v_ashrrev_i32_e32 v26, 3, v3
	v_ashrrev_i32_e32 v27, 31, v26
	v_lshl_add_u64 v[26:27], v[26:27], 2, v[24:25]
	global_load_dword v26, v[26:27], off
	v_add_u32_e32 v3, 0x60, v41
	v_or_b32_e32 v20, v20, v178
	v_or3_b32 v20, v20, v2, v6
	v_lshl_add_u64 v[192:193], v[8:9], 0, v[20:21]
	s_waitcnt vmcnt(0)
	v_ashrrev_i32_e32 v27, 31, v26
	v_lshlrev_b64 v[26:27], 17, v[26:27]
	v_lshl_add_u64 v[30:31], v[10:11], 0, v[26:27]
	v_lshl_add_u64 v[36:37], v[30:31], 0, v[6:7]
	v_ashrrev_i32_e32 v30, 3, v3
	v_add_u32_e32 v3, 0x70, v41
	v_ashrrev_i32_e32 v42, 3, v3
	v_ashrrev_i32_e32 v31, 31, v30
	v_ashrrev_i32_e32 v43, 31, v42
	v_lshl_add_u64 v[30:31], v[30:31], 2, v[24:25]
	v_lshl_add_u64 v[24:25], v[42:43], 2, v[24:25]
	global_load_dword v30, v[30:31], off
	v_lshrrev_b32_e32 v3, 4, v180
	global_load_dword v24, v[24:25], off
	v_mul_lo_u32 v41, v3, s48
	v_lshlrev_b32_e32 v3, 3, v180
	v_and_b32_e32 v3, 0x78, v3
	s_waitcnt vmcnt(1)
	v_ashrrev_i32_e32 v31, 31, v30
	v_lshlrev_b64 v[30:31], 17, v[30:31]
	s_waitcnt vmcnt(0)
	v_ashrrev_i32_e32 v25, 31, v24
	v_lshlrev_b64 v[24:25], 17, v[24:25]
	v_lshl_add_u64 v[38:39], v[10:11], 0, v[30:31]
	v_lshl_add_u64 v[10:11], v[10:11], 0, v[24:25]
	v_lshl_add_u64 v[42:43], v[10:11], 0, v[6:7]
	v_ashrrev_i32_e32 v10, 3, v180
	v_ashrrev_i32_e32 v11, 31, v10
	v_lshlrev_b64 v[44:45], 11, v[10:11]
	v_mul_lo_u32 v48, v10, s48
	v_and_b32_e32 v10, 0x70, v40
	v_or_b32_e32 v11, s11, v203
	v_mov_b32_e32 v40, s94
	v_lshl_add_u64 v[46:47], s[58:59], 0, v[44:45]
	v_mad_u32_u24 v40, v11, s48, v40
	v_mov_b32_e32 v11, v179
	v_lshl_add_u64 v[38:39], v[38:39], 0, v[6:7]
	global_load_dwordx4 v[130:133], v[18:19], off nt
	global_load_dwordx4 v[134:137], v[22:23], off nt
	global_load_dwordx4 v[138:141], v[28:29], off nt
	global_load_dwordx4 v[142:145], v[32:33], off nt
	global_load_dwordx4 v[146:149], v[34:35], off nt
	global_load_dwordx4 v[150:153], v[36:37], off nt
	global_load_dwordx4 v[154:157], v[38:39], off nt
	global_load_dwordx4 v[158:161], v[42:43], off nt
	v_lshl_add_u64 v[22:23], v[46:47], 0, v[10:11]
	v_add_co_u32_e32 v28, vcc, s2, v22
	s_mov_b32 s2, 0x40000
	s_nop 0
	v_addc_co_u32_e32 v29, vcc, 0, v23, vcc
	global_load_dwordx4 v[162:165], v[22:23], off
	global_load_dwordx4 v[166:169], v[28:29], off
	v_add_co_u32_e32 v28, vcc, s2, v22
	s_mov_b32 s2, 0x60000
	s_nop 0
	v_addc_co_u32_e32 v29, vcc, 0, v23, vcc
	v_add_co_u32_e32 v22, vcc, s2, v22
	global_load_dwordx4 v[170:173], v[28:29], off
	s_nop 0
	v_addc_co_u32_e32 v23, vcc, 0, v23, vcc
	global_load_dwordx4 v[174:177], v[22:23], off
	v_or_b32_e32 v22, v24, v178
	v_or_b32_e32 v7, s6, v203
	v_or3_b32 v24, v22, v2, v6
	v_or_b32_e32 v22, v30, v178
	v_mul_lo_u32 v49, v7, s48
	v_or3_b32 v30, v22, v2, v6
	v_or_b32_e32 v22, v26, v178
	v_lshlrev_b32_e32 v7, 4, v181
	v_add_u32_e32 v11, s94, v41
	v_add_u32_e32 v18, s94, v48
	v_add_u32_e32 v19, s94, v49
	v_or_b32_e32 v44, v44, v10
	v_or3_b32 v26, v22, v2, v6
	v_mov_b32_e32 v2, 0
	v_lshl_add_u64 v[184:185], s[74:75], 0, v[44:45]
	v_lshl_add_u64 v[186:187], v[8:9], 0, v[24:25]
	v_lshl_add_u64 v[188:189], v[8:9], 0, v[30:31]
	v_lshl_add_u64 v[190:191], v[8:9], 0, v[26:27]
	v_add_u32_e32 v178, v11, v3
	v_add_u32_e32 v204, v18, v10
	v_add_u32_e32 v205, v19, v7
	v_add_u32_e32 v206, v40, v7
	v_mov_b32_e32 v3, v2
	v_mov_b32_e32 v4, v2
	v_mov_b32_e32 v5, v2
	v_mov_b32_e32 v6, v2
	v_mov_b32_e32 v7, v2
	v_mov_b32_e32 v8, v2
	v_mov_b32_e32 v9, v2
	v_mov_b32_e32 v10, v2
	v_mov_b32_e32 v11, v2
	v_mov_b32_e32 v12, v2
	v_mov_b32_e32 v13, v2
	v_mov_b32_e32 v14, v2
	v_mov_b32_e32 v15, v2
	v_mov_b32_e32 v16, v2
	v_mov_b32_e32 v17, v2
	v_mov_b32_e32 v18, v2
	v_mov_b32_e32 v19, v2
	v_mov_b32_e32 v20, v2
	v_mov_b32_e32 v21, v2
	v_mov_b32_e32 v22, v2
	v_mov_b32_e32 v23, v2
	v_mov_b32_e32 v24, v2
	v_mov_b32_e32 v25, v2
	v_mov_b32_e32 v26, v2
	v_mov_b32_e32 v27, v2
	v_mov_b32_e32 v28, v2
	v_mov_b32_e32 v29, v2
	v_mov_b32_e32 v30, v2
	v_mov_b32_e32 v31, v2
	v_mov_b32_e32 v32, v2
	v_mov_b32_e32 v33, v2
	v_mov_b32_e32 v34, v2
	v_mov_b32_e32 v35, v2
	v_mov_b32_e32 v36, v2
	v_mov_b32_e32 v37, v2
	v_mov_b32_e32 v38, v2
	v_mov_b32_e32 v39, v2
	v_mov_b32_e32 v40, v2
	v_mov_b32_e32 v41, v2
	v_mov_b32_e32 v42, v2
	v_mov_b32_e32 v43, v2
	v_mov_b32_e32 v44, v2
	v_mov_b32_e32 v45, v2
	v_mov_b32_e32 v46, v2
	v_mov_b32_e32 v47, v2
	v_mov_b32_e32 v48, v2
	v_mov_b32_e32 v49, v2
	v_mov_b32_e32 v50, v2
	v_mov_b32_e32 v51, v2
	v_mov_b32_e32 v52, v2
	v_mov_b32_e32 v53, v2
	v_mov_b32_e32 v54, v2
	v_mov_b32_e32 v55, v2
	v_mov_b32_e32 v56, v2
	v_mov_b32_e32 v57, v2
	v_mov_b32_e32 v58, v2
	v_mov_b32_e32 v59, v2
	v_mov_b32_e32 v60, v2
	v_mov_b32_e32 v61, v2
	v_mov_b32_e32 v62, v2
	v_mov_b32_e32 v63, v2
	v_mov_b32_e32 v64, v2
	v_mov_b32_e32 v65, v2
	v_mov_b32_e32 v66, v2
	v_mov_b32_e32 v67, v2
	v_mov_b32_e32 v68, v2
	v_mov_b32_e32 v69, v2
	v_mov_b32_e32 v70, v2
	v_mov_b32_e32 v71, v2
	v_mov_b32_e32 v72, v2
	v_mov_b32_e32 v73, v2
	v_mov_b32_e32 v74, v2
	v_mov_b32_e32 v75, v2
	v_mov_b32_e32 v76, v2
	v_mov_b32_e32 v77, v2
	v_mov_b32_e32 v78, v2
	v_mov_b32_e32 v79, v2
	v_mov_b32_e32 v80, v2
	v_mov_b32_e32 v81, v2
	v_mov_b32_e32 v82, v2
	v_mov_b32_e32 v83, v2
	v_mov_b32_e32 v84, v2
	v_mov_b32_e32 v85, v2
	v_mov_b32_e32 v86, v2
	v_mov_b32_e32 v87, v2
	v_mov_b32_e32 v88, v2
	v_mov_b32_e32 v89, v2
	v_mov_b32_e32 v90, v2
	v_mov_b32_e32 v91, v2
	v_mov_b32_e32 v92, v2
	v_mov_b32_e32 v93, v2
	v_mov_b32_e32 v94, v2
	v_mov_b32_e32 v95, v2
	v_mov_b32_e32 v96, v2
	v_mov_b32_e32 v97, v2
	v_mov_b32_e32 v98, v2
	v_mov_b32_e32 v99, v2
	v_mov_b32_e32 v100, v2
	v_mov_b32_e32 v101, v2
	v_mov_b32_e32 v102, v2
	v_mov_b32_e32 v103, v2
	v_mov_b32_e32 v104, v2
	v_mov_b32_e32 v105, v2
	v_mov_b32_e32 v106, v2
	v_mov_b32_e32 v107, v2
	v_mov_b32_e32 v108, v2
	v_mov_b32_e32 v109, v2
	v_mov_b32_e32 v110, v2
	v_mov_b32_e32 v111, v2
	v_mov_b32_e32 v112, v2
	v_mov_b32_e32 v113, v2
	v_mov_b32_e32 v114, v2
	v_mov_b32_e32 v115, v2
	v_mov_b32_e32 v116, v2
	v_mov_b32_e32 v117, v2
	v_mov_b32_e32 v118, v2
	v_mov_b32_e32 v119, v2
	v_mov_b32_e32 v120, v2
	v_mov_b32_e32 v121, v2
	v_mov_b32_e32 v122, v2
	v_mov_b32_e32 v123, v2
	v_mov_b32_e32 v124, v2
	v_mov_b32_e32 v125, v2
	v_mov_b32_e32 v126, v2
	v_mov_b32_e32 v127, v2
	v_mov_b32_e32 v128, v2
	v_mov_b32_e32 v129, v2
	s_branch .LBB0_4201

.LBB0_4203:
	s_ashr_i32 s7, s6, 31
	s_lshl_b64 s[6:7], s[6:7], 10
	s_add_u32 s2, s36, s6
	s_addc_u32 s5, s37, s7
	s_lshl_b32 s6, s11, 2
	s_add_u32 s6, s2, s6
	s_addc_u32 s7, s5, 0
	v_lshlrev_b32_e32 v178, 2, v203
	s_waitcnt vmcnt(0)
	v_lshl_add_u64 v[130:131], s[6:7], 0, v[178:179]
	v_lshlrev_b32_e32 v178, 12, v181
	v_lshl_add_u64 v[132:133], v[130:131], 0, v[178:179]
	global_store_dword v[132:133], v114, off
	global_store_dword v[132:133], v115, off offset:1024
	global_store_dword v[132:133], v116, off offset:2048
	global_store_dword v[132:133], v117, off offset:3072
	v_or_b32_e32 v114, 0x2000, v178
	v_mov_b32_e32 v115, v179
	v_lshl_add_u64 v[116:117], v[130:131], 0, v[114:115]
	global_store_dword v[116:117], v118, off
	v_or_b32_e32 v116, 0x2400, v178
	v_mov_b32_e32 v117, v179
	v_lshl_add_u64 v[134:135], v[130:131], 0, v[116:117]
	global_store_dword v[134:135], v119, off
	v_or_b32_e32 v118, 0x2800, v178
	v_mov_b32_e32 v119, v179
	v_lshl_add_u64 v[134:135], v[130:131], 0, v[118:119]
	global_store_dword v[134:135], v120, off
	v_or_b32_e32 v134, 0x2c00, v178
	v_mov_b32_e32 v135, v179
	v_lshl_add_u64 v[136:137], v[130:131], 0, v[134:135]
	global_store_dword v[136:137], v121, off
	v_or_b32_e32 v120, 0x4000, v178
	v_mov_b32_e32 v121, v179
	v_lshl_add_u64 v[136:137], v[130:131], 0, v[120:121]
	global_store_dword v[136:137], v122, off
	v_or_b32_e32 v136, 0x4400, v178
	v_mov_b32_e32 v137, v179
	v_lshl_add_u64 v[138:139], v[130:131], 0, v[136:137]
	global_store_dword v[138:139], v123, off
	v_or_b32_e32 v122, 0x4800, v178
	v_mov_b32_e32 v123, v179
	v_lshl_add_u64 v[138:139], v[130:131], 0, v[122:123]
	global_store_dword v[138:139], v124, off
	v_or_b32_e32 v138, 0x4c00, v178
	v_mov_b32_e32 v139, v179
	v_lshl_add_u64 v[140:141], v[130:131], 0, v[138:139]
	global_store_dword v[140:141], v125, off
	v_or_b32_e32 v124, 0x6000, v178
	v_mov_b32_e32 v125, v179
	v_lshl_add_u64 v[140:141], v[130:131], 0, v[124:125]
	global_store_dword v[140:141], v126, off
	v_or_b32_e32 v140, 0x6400, v178
	v_mov_b32_e32 v141, v179
	v_lshl_add_u64 v[142:143], v[130:131], 0, v[140:141]
	global_store_dword v[142:143], v127, off
	v_or_b32_e32 v126, 0x6800, v178
	v_mov_b32_e32 v127, v179
	v_lshl_add_u64 v[142:143], v[130:131], 0, v[126:127]
	global_store_dword v[142:143], v128, off
	v_or_b32_e32 v142, 0x6c00, v178
	v_mov_b32_e32 v143, v179
	v_lshl_add_u64 v[144:145], v[130:131], 0, v[142:143]
	global_store_dword v[144:145], v129, off
	v_lshl_add_u64 v[128:129], v[130:131], 0, s[84:85]
	global_store_dword v[132:133], v98, off offset:128
	global_store_dword v[132:133], v99, off offset:1152
	global_store_dword v[132:133], v100, off offset:2176
	global_store_dword v[132:133], v101, off offset:3200
	v_lshl_add_u64 v[98:99], v[128:129], 0, v[114:115]
	global_store_dword v[98:99], v102, off
	v_lshl_add_u64 v[98:99], v[128:129], 0, v[116:117]
	global_store_dword v[98:99], v103, off
	v_lshl_add_u64 v[98:99], v[128:129], 0, v[118:119]
	global_store_dword v[98:99], v104, off
	v_lshl_add_u64 v[98:99], v[128:129], 0, v[134:135]
	global_store_dword v[98:99], v105, off
	v_lshl_add_u64 v[98:99], v[128:129], 0, v[120:121]
	global_store_dword v[98:99], v106, off
	v_lshl_add_u64 v[98:99], v[128:129], 0, v[136:137]
	global_store_dword v[98:99], v107, off
	v_lshl_add_u64 v[98:99], v[128:129], 0, v[122:123]
	global_store_dword v[98:99], v108, off
	v_lshl_add_u64 v[98:99], v[128:129], 0, v[138:139]
	global_store_dword v[98:99], v109, off
	v_lshl_add_u64 v[98:99], v[128:129], 0, v[124:125]
	global_store_dword v[98:99], v110, off
	v_lshl_add_u64 v[98:99], v[128:129], 0, v[140:141]
	global_store_dword v[98:99], v111, off
	v_lshl_add_u64 v[98:99], v[128:129], 0, v[126:127]
	global_store_dword v[98:99], v112, off
	v_lshl_add_u64 v[98:99], v[128:129], 0, v[142:143]
	s_mov_b64 s[6:7], 0x100
	global_store_dword v[98:99], v113, off
	v_lshl_add_u64 v[98:99], v[130:131], 0, s[6:7]
	global_store_dword v[132:133], v82, off offset:256
	global_store_dword v[132:133], v83, off offset:1280
	global_store_dword v[132:133], v84, off offset:2304
	global_store_dword v[132:133], v85, off offset:3328
	v_lshl_add_u64 v[82:83], v[98:99], 0, v[114:115]
	global_store_dword v[82:83], v86, off
	v_lshl_add_u64 v[82:83], v[98:99], 0, v[116:117]
	global_store_dword v[82:83], v87, off
	v_lshl_add_u64 v[82:83], v[98:99], 0, v[118:119]
	global_store_dword v[82:83], v88, off
	v_lshl_add_u64 v[82:83], v[98:99], 0, v[134:135]
	global_store_dword v[82:83], v89, off
	v_lshl_add_u64 v[82:83], v[98:99], 0, v[120:121]
	global_store_dword v[82:83], v90, off
	v_lshl_add_u64 v[82:83], v[98:99], 0, v[136:137]
	global_store_dword v[82:83], v91, off
	v_lshl_add_u64 v[82:83], v[98:99], 0, v[122:123]
	global_store_dword v[82:83], v92, off
	v_lshl_add_u64 v[82:83], v[98:99], 0, v[138:139]
	global_store_dword v[82:83], v93, off
	v_lshl_add_u64 v[82:83], v[98:99], 0, v[124:125]
	global_store_dword v[82:83], v94, off
	v_lshl_add_u64 v[82:83], v[98:99], 0, v[140:141]
	global_store_dword v[82:83], v95, off
	v_lshl_add_u64 v[82:83], v[98:99], 0, v[126:127]
	global_store_dword v[82:83], v96, off
	v_lshl_add_u64 v[82:83], v[98:99], 0, v[142:143]
	s_mov_b64 s[6:7], 0x180
	global_store_dword v[82:83], v97, off
	v_lshl_add_u64 v[82:83], v[130:131], 0, s[6:7]
	global_store_dword v[132:133], v66, off offset:384
	global_store_dword v[132:133], v67, off offset:1408
	global_store_dword v[132:133], v68, off offset:2432
	global_store_dword v[132:133], v69, off offset:3456
	v_lshl_add_u64 v[66:67], v[82:83], 0, v[114:115]
	global_store_dword v[66:67], v70, off
	v_lshl_add_u64 v[66:67], v[82:83], 0, v[116:117]
	global_store_dword v[66:67], v71, off
	v_lshl_add_u64 v[66:67], v[82:83], 0, v[118:119]
	global_store_dword v[66:67], v72, off
	v_lshl_add_u64 v[66:67], v[82:83], 0, v[134:135]
	global_store_dword v[66:67], v73, off
	v_lshl_add_u64 v[66:67], v[82:83], 0, v[120:121]
	global_store_dword v[66:67], v74, off
	v_lshl_add_u64 v[66:67], v[82:83], 0, v[136:137]
	global_store_dword v[66:67], v75, off
	v_lshl_add_u64 v[66:67], v[82:83], 0, v[122:123]
	global_store_dword v[66:67], v76, off
	v_lshl_add_u64 v[66:67], v[82:83], 0, v[138:139]
	global_store_dword v[66:67], v77, off
	v_lshl_add_u64 v[66:67], v[82:83], 0, v[124:125]
	global_store_dword v[66:67], v78, off
	v_lshl_add_u64 v[66:67], v[82:83], 0, v[140:141]
	global_store_dword v[66:67], v79, off
	v_lshl_add_u64 v[66:67], v[82:83], 0, v[126:127]
	global_store_dword v[66:67], v80, off
	v_lshl_add_u64 v[66:67], v[82:83], 0, v[142:143]
	global_store_dword v[66:67], v81, off
	v_or_b32_e32 v66, 0x8000, v178
	v_mov_b32_e32 v67, v179
	v_lshl_add_u64 v[68:69], v[130:131], 0, v[66:67]
	global_store_dword v[68:69], v50, off
	v_or_b32_e32 v68, 0x8400, v178
	v_mov_b32_e32 v69, v179
	v_lshl_add_u64 v[70:71], v[130:131], 0, v[68:69]
	global_store_dword v[70:71], v51, off
	v_or_b32_e32 v50, 0x8800, v178
	v_mov_b32_e32 v51, v179
	v_lshl_add_u64 v[70:71], v[130:131], 0, v[50:51]
	global_store_dword v[70:71], v52, off
	v_or_b32_e32 v70, 0x8c00, v178
	v_mov_b32_e32 v71, v179
	v_lshl_add_u64 v[72:73], v[130:131], 0, v[70:71]
	global_store_dword v[72:73], v53, off
	v_or_b32_e32 v52, 0xa000, v178
	v_mov_b32_e32 v53, v179
	v_lshl_add_u64 v[72:73], v[130:131], 0, v[52:53]
	global_store_dword v[72:73], v54, off
	v_or_b32_e32 v72, 0xa400, v178
	v_mov_b32_e32 v73, v179
	v_lshl_add_u64 v[74:75], v[130:131], 0, v[72:73]
	global_store_dword v[74:75], v55, off
	v_or_b32_e32 v54, 0xa800, v178
	v_mov_b32_e32 v55, v179
	v_lshl_add_u64 v[74:75], v[130:131], 0, v[54:55]
	global_store_dword v[74:75], v56, off
	v_or_b32_e32 v74, 0xac00, v178
	v_mov_b32_e32 v75, v179
	v_lshl_add_u64 v[76:77], v[130:131], 0, v[74:75]
	global_store_dword v[76:77], v57, off
	v_or_b32_e32 v56, 0xc000, v178
	v_mov_b32_e32 v57, v179
	v_lshl_add_u64 v[76:77], v[130:131], 0, v[56:57]
	global_store_dword v[76:77], v58, off
	v_or_b32_e32 v76, 0xc400, v178
	v_mov_b32_e32 v77, v179
	v_lshl_add_u64 v[78:79], v[130:131], 0, v[76:77]
	global_store_dword v[78:79], v59, off
	v_or_b32_e32 v58, 0xc800, v178
	v_mov_b32_e32 v59, v179
	v_lshl_add_u64 v[78:79], v[130:131], 0, v[58:59]
	global_store_dword v[78:79], v60, off
	v_or_b32_e32 v78, 0xcc00, v178
	v_mov_b32_e32 v79, v179
	v_lshl_add_u64 v[80:81], v[130:131], 0, v[78:79]
	global_store_dword v[80:81], v61, off
	v_or_b32_e32 v60, 0xe000, v178
	v_mov_b32_e32 v61, v179
	v_lshl_add_u64 v[80:81], v[130:131], 0, v[60:61]
	global_store_dword v[80:81], v62, off
	v_or_b32_e32 v80, 0xe400, v178
	v_mov_b32_e32 v81, v179
	v_lshl_add_u64 v[84:85], v[130:131], 0, v[80:81]
	global_store_dword v[84:85], v63, off
	v_or_b32_e32 v62, 0xe800, v178
	v_mov_b32_e32 v63, v179
	v_lshl_add_u64 v[84:85], v[130:131], 0, v[62:63]
	v_or_b32_e32 v178, 0xec00, v178
	global_store_dword v[84:85], v64, off
	v_lshl_add_u64 v[84:85], v[130:131], 0, v[178:179]
	global_store_dword v[84:85], v65, off
	v_lshl_add_u64 v[64:65], v[128:129], 0, v[66:67]
	global_store_dword v[64:65], v34, off
	v_lshl_add_u64 v[64:65], v[128:129], 0, v[68:69]
	global_store_dword v[64:65], v35, off
	v_lshl_add_u64 v[34:35], v[128:129], 0, v[50:51]
	global_store_dword v[34:35], v36, off
	v_lshl_add_u64 v[34:35], v[128:129], 0, v[70:71]
	global_store_dword v[34:35], v37, off
	v_lshl_add_u64 v[34:35], v[128:129], 0, v[52:53]
	global_store_dword v[34:35], v38, off
	v_lshl_add_u64 v[34:35], v[128:129], 0, v[72:73]
	global_store_dword v[34:35], v39, off
	v_lshl_add_u64 v[34:35], v[128:129], 0, v[54:55]
	global_store_dword v[34:35], v40, off
	v_lshl_add_u64 v[34:35], v[128:129], 0, v[74:75]
	global_store_dword v[34:35], v41, off
	v_lshl_add_u64 v[34:35], v[128:129], 0, v[56:57]
	global_store_dword v[34:35], v42, off
	v_lshl_add_u64 v[34:35], v[128:129], 0, v[76:77]
	global_store_dword v[34:35], v43, off
	v_lshl_add_u64 v[34:35], v[128:129], 0, v[58:59]
	global_store_dword v[34:35], v44, off
	v_lshl_add_u64 v[34:35], v[128:129], 0, v[78:79]
	global_store_dword v[34:35], v45, off
	v_lshl_add_u64 v[34:35], v[128:129], 0, v[60:61]
	global_store_dword v[34:35], v46, off
	v_lshl_add_u64 v[34:35], v[128:129], 0, v[80:81]
	global_store_dword v[34:35], v47, off
	v_lshl_add_u64 v[34:35], v[128:129], 0, v[62:63]
	global_store_dword v[34:35], v48, off
	v_lshl_add_u64 v[34:35], v[128:129], 0, v[178:179]
	global_store_dword v[34:35], v49, off
	v_lshl_add_u64 v[34:35], v[98:99], 0, v[66:67]
	global_store_dword v[34:35], v18, off
	v_lshl_add_u64 v[34:35], v[98:99], 0, v[68:69]
	global_store_dword v[34:35], v19, off
	v_lshl_add_u64 v[18:19], v[98:99], 0, v[50:51]
	global_store_dword v[18:19], v20, off
	v_lshl_add_u64 v[18:19], v[98:99], 0, v[70:71]
	global_store_dword v[18:19], v21, off
	v_lshl_add_u64 v[18:19], v[98:99], 0, v[52:53]
	global_store_dword v[18:19], v22, off
	v_lshl_add_u64 v[18:19], v[98:99], 0, v[72:73]
	global_store_dword v[18:19], v23, off
	v_lshl_add_u64 v[18:19], v[98:99], 0, v[54:55]
	global_store_dword v[18:19], v24, off
	v_lshl_add_u64 v[18:19], v[98:99], 0, v[74:75]
	global_store_dword v[18:19], v25, off
	v_lshl_add_u64 v[18:19], v[98:99], 0, v[56:57]
	global_store_dword v[18:19], v26, off
	v_lshl_add_u64 v[18:19], v[98:99], 0, v[76:77]
	global_store_dword v[18:19], v27, off
	v_lshl_add_u64 v[18:19], v[98:99], 0, v[58:59]
	global_store_dword v[18:19], v28, off
	v_lshl_add_u64 v[18:19], v[98:99], 0, v[78:79]
	global_store_dword v[18:19], v29, off
	v_lshl_add_u64 v[18:19], v[98:99], 0, v[60:61]
	global_store_dword v[18:19], v30, off
	v_lshl_add_u64 v[18:19], v[98:99], 0, v[80:81]
	global_store_dword v[18:19], v31, off
	v_lshl_add_u64 v[18:19], v[98:99], 0, v[62:63]
	global_store_dword v[18:19], v32, off
	v_lshl_add_u64 v[18:19], v[98:99], 0, v[178:179]
	global_store_dword v[18:19], v33, off
	v_lshl_add_u64 v[18:19], v[82:83], 0, v[66:67]
	global_store_dword v[18:19], v2, off
	v_lshl_add_u64 v[18:19], v[82:83], 0, v[68:69]
	global_store_dword v[18:19], v3, off
	v_lshl_add_u64 v[2:3], v[82:83], 0, v[50:51]
	global_store_dword v[2:3], v4, off
	v_lshl_add_u64 v[2:3], v[82:83], 0, v[70:71]
	global_store_dword v[2:3], v5, off
	v_lshl_add_u64 v[2:3], v[82:83], 0, v[52:53]
	global_store_dword v[2:3], v6, off
	v_lshl_add_u64 v[2:3], v[82:83], 0, v[72:73]
	global_store_dword v[2:3], v7, off
	v_lshl_add_u64 v[2:3], v[82:83], 0, v[54:55]
	global_store_dword v[2:3], v8, off
	v_lshl_add_u64 v[2:3], v[82:83], 0, v[74:75]
	global_store_dword v[2:3], v9, off
	v_lshl_add_u64 v[2:3], v[82:83], 0, v[56:57]
	global_store_dword v[2:3], v10, off
	v_lshl_add_u64 v[2:3], v[82:83], 0, v[76:77]
	global_store_dword v[2:3], v11, off
	v_lshl_add_u64 v[2:3], v[82:83], 0, v[58:59]
	global_store_dword v[2:3], v12, off
	v_lshl_add_u64 v[2:3], v[82:83], 0, v[78:79]
	global_store_dword v[2:3], v13, off
	v_lshl_add_u64 v[2:3], v[82:83], 0, v[60:61]
	global_store_dword v[2:3], v14, off
	v_lshl_add_u64 v[2:3], v[82:83], 0, v[80:81]
	global_store_dword v[2:3], v15, off
	v_lshl_add_u64 v[2:3], v[82:83], 0, v[62:63]
	global_store_dword v[2:3], v16, off
	v_lshl_add_u64 v[2:3], v[82:83], 0, v[178:179]
	s_mov_b64 s[6:7], 0
	global_store_dword v[2:3], v17, off
	s_waitcnt lgkmcnt(0)
	s_barrier

.LBB0_4209:
	s_lshl_b32 s24, s86, 4
	s_lshl_b32 s25, s86, 6
	s_and_b32 s24, s24, 0xffffe000
	s_and_b32 s25, s25, 0x1fc0
	s_or_b32 s87, s24, s25
	s_bfe_u32 s88, s86, 0x20007
	v_add_u32_e32 v2, s87, v35
	v_mov_b64_e32 v[10:11], s[46:47]
	v_mad_i64_i32 v[2:3], s[24:25], v2, s62, v[10:11]
	s_lshl_b32 s56, s88, 8
	v_lshl_add_u64 v[2:3], v[2:3], 0, s[56:57]
	v_lshlrev_b32_e32 v178, 2, v182
	v_add_u32_e32 v4, s87, v36
	v_lshl_add_u64 v[2:3], v[2:3], 0, v[178:179]
	v_mad_i64_i32 v[4:5], s[24:25], v4, s62, v[10:11]
	v_add_co_u32_e32 v2, vcc, s30, v2
	v_lshl_add_u64 v[4:5], v[4:5], 0, s[56:57]
	v_add_u32_e32 v6, s87, v37
	v_addc_co_u32_e32 v3, vcc, 0, v3, vcc
	v_lshl_add_u64 v[4:5], v[4:5], 0, v[178:179]
	v_mad_i64_i32 v[6:7], s[24:25], v6, s62, v[10:11]
	v_add_co_u32_e32 v4, vcc, s30, v4
	v_lshl_add_u64 v[6:7], v[6:7], 0, s[56:57]
	v_add_u32_e32 v8, s87, v38
	v_addc_co_u32_e32 v5, vcc, 0, v5, vcc
	v_lshl_add_u64 v[6:7], v[6:7], 0, v[178:179]
	v_mad_i64_i32 v[8:9], s[24:25], v8, s62, v[10:11]
	v_add_co_u32_e32 v6, vcc, s30, v6
	v_lshl_add_u64 v[8:9], v[8:9], 0, s[56:57]
	v_add_u32_e32 v12, s87, v39
	v_addc_co_u32_e32 v7, vcc, 0, v7, vcc
	v_lshl_add_u64 v[8:9], v[8:9], 0, v[178:179]
	v_mad_i64_i32 v[12:13], s[24:25], v12, s62, v[10:11]
	v_add_co_u32_e32 v8, vcc, s30, v8
	v_lshl_add_u64 v[12:13], v[12:13], 0, s[56:57]
	v_add_u32_e32 v14, s87, v40
	v_addc_co_u32_e32 v9, vcc, 0, v9, vcc
	v_lshl_add_u64 v[12:13], v[12:13], 0, v[178:179]
	v_mad_i64_i32 v[14:15], s[24:25], v14, s62, v[10:11]
	v_add_co_u32_e32 v12, vcc, s30, v12
	v_lshl_add_u64 v[14:15], v[14:15], 0, s[56:57]
	v_add_u32_e32 v16, s87, v41
	v_addc_co_u32_e32 v13, vcc, 0, v13, vcc
	v_lshl_add_u64 v[14:15], v[14:15], 0, v[178:179]
	v_mad_i64_i32 v[16:17], s[24:25], v16, s62, v[10:11]
	v_add_co_u32_e32 v14, vcc, s30, v14
	v_lshl_add_u64 v[16:17], v[16:17], 0, s[56:57]
	v_add_u32_e32 v29, s87, v42
	v_addc_co_u32_e32 v15, vcc, 0, v15, vcc
	v_lshl_add_u64 v[16:17], v[16:17], 0, v[178:179]
	v_mad_i64_i32 v[66:67], s[24:25], v29, s62, v[10:11]
	v_add_co_u32_e32 v16, vcc, s30, v16
	v_lshl_add_u64 v[66:67], v[66:67], 0, s[56:57]
	s_nop 0
	v_addc_co_u32_e32 v17, vcc, 0, v17, vcc
	v_lshl_add_u64 v[66:67], v[66:67], 0, v[178:179]
	v_add_co_u32_e32 v74, vcc, s30, v66
	s_lshl_b32 s56, s88, 9
	s_nop 0
	v_addc_co_u32_e32 v75, vcc, 0, v67, vcc
	global_load_dword v72, v[2:3], off offset:2144
	global_load_dword v71, v[4:5], off offset:2144
	global_load_dword v70, v[6:7], off offset:2144
	global_load_dword v69, v[8:9], off offset:2144
	global_load_dword v68, v[12:13], off offset:2144
	global_load_dword v67, v[14:15], off offset:2144
	global_load_dword v66, v[16:17], off offset:2144
	global_load_dword v65, v[74:75], off offset:2144
	v_add_u32_e32 v2, s87, v44
	v_mad_i64_i32 v[2:3], s[24:25], v2, s62, v[10:11]
	v_lshl_add_u64 v[2:3], v[2:3], 0, s[56:57]
	v_mov_b32_e32 v29, v179
	v_add_u32_e32 v4, s87, v45
	v_lshl_add_u64 v[2:3], v[2:3], 0, v[28:29]
	v_mad_i64_i32 v[4:5], s[24:25], v4, s62, v[10:11]
	v_add_co_u32_e32 v2, vcc, s30, v2
	v_lshl_add_u64 v[4:5], v[4:5], 0, s[56:57]
	v_add_u32_e32 v12, s87, v46
	v_addc_co_u32_e32 v3, vcc, 0, v3, vcc
	v_lshl_add_u64 v[4:5], v[4:5], 0, v[28:29]
	v_mad_i64_i32 v[12:13], s[24:25], v12, s62, v[10:11]
	v_add_co_u32_e32 v6, vcc, s30, v4
	v_lshl_add_u64 v[12:13], v[12:13], 0, s[56:57]
	v_add_u32_e32 v14, s87, v47
	v_addc_co_u32_e32 v7, vcc, 0, v5, vcc
	v_lshl_add_u64 v[12:13], v[12:13], 0, v[28:29]
	v_mad_i64_i32 v[10:11], s[24:25], v14, s62, v[10:11]
	v_add_co_u32_e32 v12, vcc, s30, v12
	v_lshl_add_u64 v[10:11], v[10:11], 0, s[56:57]
	s_nop 0
	v_addc_co_u32_e32 v13, vcc, 0, v13, vcc
	v_lshl_add_u64 v[10:11], v[10:11], 0, v[28:29]
	v_add_co_u32_e32 v14, vcc, 0x1000, v10
	global_load_dwordx4 v[2:5], v[2:3], off offset:3168
	s_nop 0
	global_load_dwordx4 v[6:9], v[6:7], off offset:3168
	v_addc_co_u32_e32 v15, vcc, 0, v11, vcc
	global_load_dwordx4 v[10:13], v[12:13], off offset:3168
	s_nop 0
	global_load_dwordx4 v[14:17], v[14:15], off offset:3168
	s_lshl_b32 s88, s88, 6
	s_mov_b32 s89, s57
	s_waitcnt vmcnt(0) lgkmcnt(0)
	s_barrier
	s_and_saveexec_b64 s[24:25], s[6:7]
	s_cbranch_execz .LBB0_4214
	s_mov_b64 s[90:91], 0
	v_mov_b32_e32 v29, v180
.LBB0_4211:
	v_ashrrev_i32_e32 v73, 4, v29
	v_add_u32_e32 v74, s87, v73
	v_mad_i64_i32 v[74:75], s[92:93], v74, s62, v[22:23]
	global_load_dword v74, v[74:75], off
	v_add_u32_e32 v75, 0x200, v29
	v_cmp_lt_i32_e32 vcc, s63, v29
	v_lshl_add_u32 v73, v73, 2, v59
	s_or_b64 s[90:91], vcc, s[90:91]
	v_mov_b32_e32 v29, v75
	s_waitcnt vmcnt(0) lgkmcnt(0)
	ds_write_b32 v73, v74
	s_andn2_b64 exec, exec, s[90:91]
	s_cbranch_execnz .LBB0_4211
	s_or_b64 exec, exec, s[90:91]
	s_mov_b64 s[90:91], 0
	v_mov_b32_e32 v29, v43
	v_mov_b32_e32 v73, v61
.LBB0_4213:
	v_mov_b64_e32 v[74:75], s[0:1]
	global_load_dwordx2 v[74:75], v[74:75], off offset:152 sc0 sc1
	s_waitcnt vmcnt(0)
	v_and_b32_e32 v76, 0xffffff00, v29
	v_ashrrev_i32_e32 v77, 31, v76
	s_lshl_b32 s56, s88, 2
	v_add_u32_e32 v73, 0x200, v73
	s_waitcnt lgkmcnt(0)
	v_lshl_add_u64 v[74:75], v[76:77], 2, v[74:75]
	v_lshl_add_u64 v[74:75], v[74:75], 0, s[56:57]
	v_lshl_add_u64 v[74:75], v[74:75], 0, v[178:179]
	v_add_co_u32_e32 v74, vcc, 0x4000, v74
	s_nop 1
	v_addc_co_u32_e32 v75, vcc, 0, v75, vcc
	global_load_dword v74, v[74:75], off
	v_cmp_lt_i32_e32 vcc, s63, v73
	v_add_u32_e32 v75, s4, v29
	v_add_u32_e32 v29, 0x800, v29
	s_or_b64 s[90:91], vcc, s[90:91]
	s_waitcnt vmcnt(0)
	ds_write_b32 v75, v74
	s_andn2_b64 exec, exec, s[90:91]
	s_cbranch_execnz .LBB0_4213

.LBB0_4216:
	v_mov_b64_e32 v[76:77], s[0:1]
	global_load_dwordx2 v[76:77], v[76:77], off offset:160 sc0 sc1
	s_waitcnt vmcnt(0)
	v_ashrrev_i32_e32 v74, 6, v29
	v_ashrrev_i32_e32 v75, 31, v74
	v_lshl_add_u64 v[78:79], s[88:89], 0, v[74:75]
	v_lshl_add_u32 v75, v74, 2, s4
	s_mov_b32 s24, 0xbfb8aa3b
	s_waitcnt lgkmcnt(0)
	v_lshl_add_u64 v[76:77], v[78:79], 2, v[76:77]
	global_load_dword v73, v[76:77], off offset:1024
	ds_read2st64_b32 v[76:77], v60 offset1:1
	ds_read2st64_b32 v[78:79], v75 offset1:1
	s_waitcnt vmcnt(0) lgkmcnt(0)
	v_fmac_f32_e32 v73, v76, v78
	v_fmac_f32_e32 v73, v77, v79
	ds_read2st64_b32 v[76:77], v60 offset0:2 offset1:3
	ds_read2st64_b32 v[78:79], v75 offset0:2 offset1:3
	s_waitcnt lgkmcnt(0)
	v_fmac_f32_e32 v73, v76, v78
	v_fmac_f32_e32 v73, v77, v79
	ds_read2st64_b32 v[76:77], v60 offset0:4 offset1:5
	ds_read2st64_b32 v[78:79], v75 offset0:4 offset1:5
	s_waitcnt lgkmcnt(0)
	v_fmac_f32_e32 v73, v76, v78
	v_fmac_f32_e32 v73, v77, v79
	ds_read2st64_b32 v[76:77], v60 offset0:6 offset1:7
	ds_read2st64_b32 v[78:79], v75 offset0:6 offset1:7
	s_waitcnt lgkmcnt(0)
	v_pk_mul_f32 v[76:77], v[76:77], v[78:79]
	s_nop 0
	v_add_f32_e32 v73, v73, v76
	v_add_f32_e32 v73, v73, v77
	ds_read2st64_b32 v[76:77], v60 offset0:8 offset1:9
	ds_read2st64_b32 v[78:79], v75 offset0:8 offset1:9
	s_waitcnt lgkmcnt(0)
	v_pk_mul_f32 v[76:77], v[76:77], v[78:79]
	s_nop 0
	v_add_f32_e32 v73, v73, v76
	v_add_f32_e32 v73, v73, v77
	ds_read2st64_b32 v[76:77], v60 offset0:10 offset1:11
	ds_read2st64_b32 v[78:79], v75 offset0:10 offset1:11
	s_waitcnt lgkmcnt(0)
	v_pk_mul_f32 v[76:77], v[76:77], v[78:79]
	s_nop 0
	v_add_f32_e32 v73, v73, v76
	v_add_f32_e32 v73, v73, v77
	ds_read2st64_b32 v[76:77], v60 offset0:12 offset1:13
	ds_read2st64_b32 v[78:79], v75 offset0:12 offset1:13
	s_waitcnt lgkmcnt(0)
	v_pk_mul_f32 v[76:77], v[76:77], v[78:79]
	s_nop 0
	v_add_f32_e32 v73, v73, v76
	v_add_f32_e32 v73, v73, v77
	ds_read2st64_b32 v[76:77], v60 offset0:14 offset1:15
	ds_read2st64_b32 v[78:79], v75 offset0:14 offset1:15
	s_waitcnt lgkmcnt(0)
	v_pk_mul_f32 v[76:77], v[76:77], v[78:79]
	s_nop 0
	v_add_f32_e32 v73, v73, v76
	v_add_f32_e32 v73, v73, v77
	v_min_f32_e32 v75, 0, v73
	v_mul_f32_e64 v73, |v73|, s24
	v_exp_f32_e32 v73, v73
	s_mov_b32 s24, 0x800000
	v_add_f32_e32 v73, 1.0, v73
	v_cmp_gt_f32_e32 vcc, s24, v73
	s_mov_b32 s24, 0x3f317217
	s_nop 0
	v_cndmask_b32_e64 v76, 0, 32, vcc
	v_ldexp_f32 v73, v73, v76
	v_log_f32_e32 v73, v73
	s_nop 0
	v_mul_f32_e32 v76, 0x3f317217, v73
	v_fma_f32 v76, v73, s24, -v76
	v_fmac_f32_e32 v76, 0x3377d1cf, v73
	s_mov_b32 s24, 0x7f800000
	v_fmac_f32_e32 v76, 0x3f317217, v73
	v_cmp_lt_f32_e64 s[24:25], |v73|, s24
	s_nop 1
	v_cndmask_b32_e64 v73, v73, v76, s[24:25]
	v_cndmask_b32_e32 v76, 0, v183, vcc
	v_sub_f32_e32 v73, v73, v76
	v_sub_f32_e32 v73, v75, v73
	v_mad_u64_u32 v[74:75], s[24:25], v74, s31, v[18:19]
	v_mul_f32_e32 v73, 0x3d800000, v73
	s_movk_i32 s24, 0xdff
	ds_write_b32 v74, v73
	v_add_u32_e32 v73, 0x200, v29
	v_cmp_lt_i32_e32 vcc, s24, v29
	s_or_b64 s[92:93], vcc, s[92:93]
	v_mov_b32_e32 v29, v73
	s_andn2_b64 exec, exec, s[92:93]
	s_cbranch_execnz .LBB0_4216
.LBB0_4217:
	s_or_b64 exec, exec, s[90:91]
	v_add_u32_e32 v29, s81, v18
	s_waitcnt lgkmcnt(0)
	s_barrier
	ds_read2_b32 v[74:75], v29 offset1:65
	s_ashr_i32 s87, s86, 31
	s_lshl_b64 s[24:25], s[86:87], 14
	s_waitcnt lgkmcnt(0)
	ds_bpermute_b32 v73, v19, v74
	ds_bpermute_b32 v76, v19, v75
	s_waitcnt lgkmcnt(1)
	v_add_f32_e32 v73, v74, v73
	s_waitcnt lgkmcnt(0)
	v_add_f32_e32 v76, v75, v76
	v_cndmask_b32_e64 v73, v73, v74, s[10:11]
	v_cndmask_b32_e64 v74, v76, v75, s[10:11]
	ds_bpermute_b32 v75, v30, v73
	ds_bpermute_b32 v76, v30, v74
	s_waitcnt lgkmcnt(1)
	v_add_f32_e32 v75, v73, v75
	v_cndmask_b32_e64 v73, v75, v73, s[12:13]
	ds_bpermute_b32 v77, v31, v73
	s_waitcnt lgkmcnt(1)
	v_add_f32_e32 v76, v74, v76
	v_cndmask_b32_e64 v76, v76, v74, s[12:13]
	ds_bpermute_b32 v78, v31, v76
	ds_read2_b32 v[74:75], v29 offset0:130 offset1:195
	s_waitcnt lgkmcnt(2)
	v_add_f32_e32 v77, v73, v77
	v_cndmask_b32_e64 v73, v77, v73, s[14:15]
	ds_bpermute_b32 v77, v32, v73
	s_waitcnt lgkmcnt(2)
	v_add_f32_e32 v78, v76, v78
	v_cndmask_b32_e64 v76, v78, v76, s[14:15]
	ds_bpermute_b32 v78, v32, v76
	s_waitcnt lgkmcnt(2)
	ds_bpermute_b32 v79, v19, v74
	s_waitcnt lgkmcnt(2)
	v_add_f32_e32 v77, v73, v77
	v_cndmask_b32_e64 v73, v77, v73, s[16:17]
	ds_bpermute_b32 v77, v33, v73
	s_waitcnt lgkmcnt(2)
	v_add_f32_e32 v78, v76, v78
	v_cndmask_b32_e64 v76, v78, v76, s[16:17]
	s_waitcnt lgkmcnt(1)
	v_add_f32_e32 v79, v74, v79
	ds_bpermute_b32 v78, v33, v76
	v_cndmask_b32_e64 v74, v79, v74, s[10:11]
	ds_bpermute_b32 v79, v30, v74
	s_waitcnt lgkmcnt(2)
	v_add_f32_e32 v77, v73, v77
	v_cndmask_b32_e64 v73, v77, v73, s[18:19]
	ds_bpermute_b32 v77, v34, v73
	s_waitcnt lgkmcnt(2)
	v_add_f32_e32 v78, v76, v78
	v_cndmask_b32_e64 v76, v78, v76, s[18:19]
	s_waitcnt lgkmcnt(1)
	v_add_f32_e32 v79, v74, v79
	ds_bpermute_b32 v78, v34, v76
	v_cndmask_b32_e64 v74, v79, v74, s[12:13]
	ds_bpermute_b32 v79, v31, v74
	s_waitcnt lgkmcnt(2)
	v_add_f32_e32 v77, v73, v77
	v_cndmask_b32_e64 v73, v77, v73, s[20:21]
	ds_bpermute_b32 v77, v19, v75
	s_waitcnt lgkmcnt(2)
	v_add_f32_e32 v78, v76, v78
	v_cndmask_b32_e64 v76, v78, v76, s[20:21]
	s_waitcnt lgkmcnt(1)
	v_add_f32_e32 v78, v74, v79
	v_cndmask_b32_e64 v74, v78, v74, s[14:15]
	s_waitcnt lgkmcnt(0)
	v_add_f32_e32 v77, v75, v77
	ds_bpermute_b32 v78, v32, v74
	v_cndmask_b32_e64 v75, v77, v75, s[10:11]
	ds_bpermute_b32 v77, v30, v75
	ds_write2_b32 v29, v73, v76 offset1:65
	s_waitcnt lgkmcnt(2)
	v_add_f32_e32 v73, v74, v78
	v_cndmask_b32_e64 v73, v73, v74, s[16:17]
	s_waitcnt lgkmcnt(1)
	v_add_f32_e32 v74, v75, v77
	v_cndmask_b32_e64 v77, v74, v75, s[12:13]
	v_add_u32_e32 v78, 0x400, v29
	ds_read2_b32 v[74:75], v78 offset0:4 offset1:69
	ds_bpermute_b32 v79, v31, v77
	ds_bpermute_b32 v76, v33, v73
	s_waitcnt lgkmcnt(2)
	ds_bpermute_b32 v80, v19, v74
	s_waitcnt lgkmcnt(2)
	v_add_f32_e32 v79, v77, v79
	v_cndmask_b32_e64 v77, v79, v77, s[14:15]
	ds_bpermute_b32 v79, v32, v77
	s_waitcnt lgkmcnt(2)
	v_add_f32_e32 v76, v73, v76
	v_cndmask_b32_e64 v73, v76, v73, s[18:19]
	s_waitcnt lgkmcnt(1)
	v_add_f32_e32 v80, v74, v80
	ds_bpermute_b32 v76, v34, v73
	v_cndmask_b32_e64 v74, v80, v74, s[10:11]
	ds_bpermute_b32 v80, v30, v74
	s_waitcnt lgkmcnt(2)
	v_add_f32_e32 v79, v77, v79
	v_cndmask_b32_e64 v77, v79, v77, s[16:17]
	ds_bpermute_b32 v79, v33, v77
	s_waitcnt lgkmcnt(2)
	v_add_f32_e32 v76, v73, v76
	v_cndmask_b32_e64 v73, v76, v73, s[20:21]
	s_waitcnt lgkmcnt(1)
	v_add_f32_e32 v76, v74, v80
	v_cndmask_b32_e64 v74, v76, v74, s[12:13]
	ds_bpermute_b32 v76, v31, v74
	s_waitcnt lgkmcnt(1)
	v_add_f32_e32 v79, v77, v79
	v_cndmask_b32_e64 v77, v79, v77, s[18:19]
	ds_bpermute_b32 v79, v19, v75
	ds_bpermute_b32 v80, v34, v77
	s_waitcnt lgkmcnt(2)
	v_add_f32_e32 v76, v74, v76
	v_cndmask_b32_e64 v74, v76, v74, s[14:15]
	ds_bpermute_b32 v76, v32, v74
	s_waitcnt lgkmcnt(2)
	v_add_f32_e32 v79, v75, v79
	v_cndmask_b32_e64 v75, v79, v75, s[10:11]
	ds_bpermute_b32 v79, v30, v75
	s_waitcnt lgkmcnt(2)
	v_add_f32_e32 v80, v77, v80
	s_waitcnt lgkmcnt(1)
	v_add_f32_e32 v76, v74, v76
	v_cndmask_b32_e64 v74, v76, v74, s[16:17]
	ds_bpermute_b32 v76, v33, v74
	s_waitcnt lgkmcnt(1)
	v_add_f32_e32 v79, v75, v79
	v_cndmask_b32_e64 v75, v79, v75, s[12:13]
	ds_bpermute_b32 v79, v31, v75
	v_cndmask_b32_e64 v77, v80, v77, s[20:21]
	s_waitcnt lgkmcnt(1)
	v_add_f32_e32 v76, v74, v76
	v_cndmask_b32_e64 v76, v76, v74, s[18:19]
	ds_write2_b32 v29, v73, v77 offset0:130 offset1:195
	s_waitcnt lgkmcnt(1)
	v_add_f32_e32 v74, v75, v79
	v_cndmask_b32_e64 v79, v74, v75, s[14:15]
	ds_read2_b32 v[74:75], v78 offset0:134 offset1:199
	ds_bpermute_b32 v80, v34, v76
	ds_bpermute_b32 v81, v32, v79
	s_waitcnt lgkmcnt(2)
	ds_bpermute_b32 v73, v19, v74
	ds_bpermute_b32 v77, v19, v75
	s_waitcnt lgkmcnt(3)
	v_add_f32_e32 v29, v76, v80
	v_cndmask_b32_e64 v29, v29, v76, s[20:21]
	s_waitcnt lgkmcnt(2)
	v_add_f32_e32 v76, v79, v81
	s_waitcnt lgkmcnt(1)
	v_add_f32_e32 v73, v74, v73
	v_cndmask_b32_e64 v73, v73, v74, s[10:11]
	s_waitcnt lgkmcnt(0)
	v_add_f32_e32 v77, v75, v77
	ds_bpermute_b32 v74, v30, v73
	v_cndmask_b32_e64 v75, v77, v75, s[10:11]
	ds_bpermute_b32 v77, v30, v75
	v_cndmask_b32_e64 v76, v76, v79, s[16:17]
	ds_bpermute_b32 v79, v33, v76
	s_waitcnt lgkmcnt(2)
	v_add_f32_e32 v74, v73, v74
	v_cndmask_b32_e64 v73, v74, v73, s[12:13]
	s_waitcnt lgkmcnt(1)
	v_add_f32_e32 v77, v75, v77
	ds_bpermute_b32 v74, v31, v73
	v_cndmask_b32_e64 v75, v77, v75, s[12:13]
	ds_bpermute_b32 v77, v31, v75
	s_waitcnt lgkmcnt(2)
	v_add_f32_e32 v79, v76, v79
	v_cndmask_b32_e64 v76, v79, v76, s[18:19]
	s_waitcnt lgkmcnt(1)
	v_add_f32_e32 v74, v73, v74
	v_cndmask_b32_e64 v73, v74, v73, s[14:15]
	s_waitcnt lgkmcnt(0)
	v_add_f32_e32 v77, v75, v77
	ds_bpermute_b32 v74, v32, v73
	v_cndmask_b32_e64 v75, v77, v75, s[14:15]
	ds_bpermute_b32 v77, v32, v75
	ds_bpermute_b32 v79, v34, v76
	s_waitcnt lgkmcnt(2)
	v_add_f32_e32 v74, v73, v74
	v_cndmask_b32_e64 v73, v74, v73, s[16:17]
	s_waitcnt lgkmcnt(1)
	v_add_f32_e32 v77, v75, v77
	ds_bpermute_b32 v74, v33, v73
	v_cndmask_b32_e64 v75, v77, v75, s[16:17]
	ds_bpermute_b32 v77, v33, v75
	s_waitcnt lgkmcnt(2)
	v_add_f32_e32 v79, v76, v79
	v_cndmask_b32_e64 v76, v79, v76, s[20:21]
	s_waitcnt lgkmcnt(1)
	v_add_f32_e32 v74, v73, v74
	v_cndmask_b32_e64 v73, v74, v73, s[18:19]
	s_waitcnt lgkmcnt(0)
	v_add_f32_e32 v77, v75, v77
	ds_bpermute_b32 v74, v34, v73
	v_cndmask_b32_e64 v75, v77, v75, s[18:19]
	ds_bpermute_b32 v77, v34, v75
	ds_write2_b32 v78, v29, v76 offset0:4 offset1:69
	s_waitcnt lgkmcnt(2)
	v_add_f32_e32 v29, v73, v74
	v_cndmask_b32_e64 v29, v29, v73, s[20:21]
	s_waitcnt lgkmcnt(1)
	v_add_f32_e32 v73, v75, v77
	v_cndmask_b32_e64 v73, v73, v75, s[20:21]
	ds_write2_b32 v78, v29, v73 offset0:134 offset1:199
	s_waitcnt lgkmcnt(0)
	s_barrier
	ds_read_b32 v29, v49
	ds_read_b32 v73, v48 offset:252
	s_waitcnt lgkmcnt(0)
	v_sub_f32_e32 v73, v73, v29
	v_mul_f32_e32 v73, 0x3fb8aa3b, v73
	v_exp_f32_e32 v73, v73
	s_nop 0
	v_mul_f32_e32 v72, v72, v73
	ds_write_b32 v50, v72 offset:16640
	v_lshl_add_u64 v[72:73], v[26:27], 0, s[24:25]
	global_store_dword v[72:73], v29, off
	ds_read_b32 v29, v51
	ds_read_b32 v74, v48 offset:252
	s_movk_i32 s24, 0x2000
	s_waitcnt lgkmcnt(0)
	v_sub_f32_e32 v74, v74, v29
	v_mul_f32_e32 v74, 0x3fb8aa3b, v74
	v_exp_f32_e32 v74, v74
	s_nop 0
	v_mul_f32_e32 v71, v71, v74
	ds_write_b32 v50, v71 offset:18688
	global_store_dword v[72:73], v29, off offset:2048
	ds_read_b32 v29, v52
	ds_read_b32 v71, v48 offset:252
	s_waitcnt lgkmcnt(0)
	v_sub_f32_e32 v71, v71, v29
	v_mul_f32_e32 v71, 0x3fb8aa3b, v71
	v_exp_f32_e32 v71, v71
	s_nop 0
	v_mul_f32_e32 v70, v70, v71
	ds_write_b32 v50, v70 offset:20736
	v_add_co_u32_e32 v70, vcc, s30, v72
	s_nop 1
	v_addc_co_u32_e32 v71, vcc, 0, v73, vcc
	global_store_dword v[70:71], v29, off
	ds_read_b32 v29, v53
	ds_read_b32 v74, v48 offset:252
	s_waitcnt lgkmcnt(0)
	v_sub_f32_e32 v74, v74, v29
	v_mul_f32_e32 v74, 0x3fb8aa3b, v74
	v_exp_f32_e32 v74, v74
	s_nop 0
	v_mul_f32_e32 v69, v69, v74
	ds_write_b32 v50, v69 offset:22784
	global_store_dword v[70:71], v29, off offset:2048
	ds_read_b32 v29, v54
	ds_read_b32 v69, v48 offset:252
	s_waitcnt lgkmcnt(0)
	v_sub_f32_e32 v69, v69, v29
	v_mul_f32_e32 v69, 0x3fb8aa3b, v69
	v_exp_f32_e32 v69, v69
	s_nop 0
	v_mul_f32_e32 v68, v68, v69
	ds_write_b32 v50, v68 offset:24832
	v_add_co_u32_e32 v68, vcc, s24, v72
	s_mov_b32 s24, 0
	s_nop 0
	v_addc_co_u32_e32 v69, vcc, 0, v73, vcc
	global_store_dword v[68:69], v29, off
	ds_read_b32 v29, v55
	ds_read_b32 v70, v48 offset:252
	s_waitcnt lgkmcnt(0)
	v_sub_f32_e32 v70, v70, v29
	v_mul_f32_e32 v70, 0x3fb8aa3b, v70
	v_exp_f32_e32 v70, v70
	s_nop 0
	v_mul_f32_e32 v67, v67, v70
	ds_write_b32 v50, v67 offset:26880
	global_store_dword v[68:69], v29, off offset:2048
	ds_read_b32 v29, v56
	ds_read_b32 v67, v48 offset:252
	s_waitcnt lgkmcnt(0)
	v_sub_f32_e32 v67, v67, v29
	v_mul_f32_e32 v67, 0x3fb8aa3b, v67
	v_exp_f32_e32 v67, v67
	s_nop 0
	v_mul_f32_e32 v66, v66, v67
	ds_write_b32 v50, v66 offset:28928
	v_add_co_u32_e32 v66, vcc, s62, v72
	s_nop 1
	v_addc_co_u32_e32 v67, vcc, 0, v73, vcc
	global_store_dword v[66:67], v29, off
	ds_read_b32 v29, v57
	ds_read_b32 v68, v48 offset:252
	s_waitcnt lgkmcnt(0)
	v_sub_f32_e32 v68, v68, v29
	v_mul_f32_e32 v68, 0x3fb8aa3b, v68
	v_exp_f32_e32 v68, v68
	s_nop 0
	v_mul_f32_e32 v65, v65, v68
	ds_write_b32 v50, v65 offset:30976
	global_store_dword v[66:67], v29, off offset:2048
	ds_write_b128 v58, v[2:5] offset:33024
	ds_write_b128 v58, v[6:9] offset:41216
	ds_write_b128 v58, v[10:13] offset:49408
	ds_write_b128 v58, v[14:17] offset:57600
	v_mov_b32_e32 v2, 0
	v_mov_b32_e32 v29, v62
	v_mov_b32_e32 v3, v2
	v_mov_b32_e32 v4, v2
	v_mov_b32_e32 v5, v2
	v_mov_b32_e32 v6, v2
	v_mov_b32_e32 v7, v2
	v_mov_b32_e32 v8, v2
	v_mov_b32_e32 v9, v2
	v_mov_b32_e32 v10, v2
	v_mov_b32_e32 v11, v2
	v_mov_b32_e32 v12, v2
	v_mov_b32_e32 v13, v2
	v_mov_b32_e32 v14, v2
	v_mov_b32_e32 v15, v2
	v_mov_b32_e32 v16, v2
	v_mov_b32_e32 v17, v2
	s_waitcnt lgkmcnt(0)
	s_barrier
.LBB0_4218:
	v_add_u32_e32 v65, s24, v63
	ds_read2st64_b32 v[66:67], v65 offset1:2
	ds_read2st64_b32 v[68:69], v29 offset1:4
	s_addk_i32 s24, 0x1000
	s_cmpk_lg_i32 s24, 0x4000
	s_waitcnt lgkmcnt(0)
	v_mfma_f32_32x32x2_f32 v[2:17], v66, v68, v[2:17]
	v_mfma_f32_32x32x2_f32 v[2:17], v67, v69, v[2:17]
	ds_read2st64_b32 v[66:67], v65 offset0:4 offset1:6
	ds_read2st64_b32 v[68:69], v29 offset0:8 offset1:12
	s_waitcnt lgkmcnt(0)
	v_mfma_f32_32x32x2_f32 v[2:17], v66, v68, v[2:17]
	v_mfma_f32_32x32x2_f32 v[2:17], v67, v69, v[2:17]
	ds_read2st64_b32 v[66:67], v65 offset0:8 offset1:10
	ds_read2st64_b32 v[68:69], v29 offset0:16 offset1:20
	s_waitcnt lgkmcnt(0)
	v_mfma_f32_32x32x2_f32 v[2:17], v66, v68, v[2:17]
	v_mfma_f32_32x32x2_f32 v[2:17], v67, v69, v[2:17]
	ds_read2st64_b32 v[66:67], v65 offset0:12 offset1:14
	ds_read2st64_b32 v[68:69], v29 offset0:24 offset1:28
	v_add_u32_e32 v29, 0x2000, v29
	s_waitcnt lgkmcnt(0)
	v_mfma_f32_32x32x2_f32 v[2:17], v66, v68, v[2:17]
	v_mfma_f32_32x32x2_f32 v[2:17], v67, v69, v[2:17]
	s_cbranch_scc1 .LBB0_4218
	s_lshl_b64 s[24:25], s[86:87], 6
	s_add_u32 s88, s24, s5
	s_addc_u32 s89, s25, s2
	s_lshl_b64 s[88:89], s[88:89], 9
	v_lshl_add_u64 v[66:67], v[24:25], 0, s[88:89]
	s_nop 11
	global_store_dword v[66:67], v2, off
	global_store_dword v[66:67], v3, off offset:512
	global_store_dword v[66:67], v4, off offset:1024
	global_store_dword v[66:67], v5, off offset:1536
	v_add_co_u32_e32 v2, vcc, 0x1000, v66
	s_nop 1
	v_addc_co_u32_e32 v3, vcc, 0, v67, vcc
	global_store_dword v[2:3], v6, off
	global_store_dword v[2:3], v7, off offset:512
	global_store_dword v[2:3], v8, off offset:1024
	global_store_dword v[2:3], v9, off offset:1536
	v_add_co_u32_e32 v2, vcc, 0x2000, v66
	s_nop 1
	v_addc_co_u32_e32 v3, vcc, 0, v67, vcc
	global_store_dword v[2:3], v10, off
	global_store_dword v[2:3], v11, off offset:512
	global_store_dword v[2:3], v12, off offset:1024
	global_store_dword v[2:3], v13, off offset:1536
	v_add_co_u32_e32 v2, vcc, 0x3000, v66
	s_nop 1
	v_addc_co_u32_e32 v3, vcc, 0, v67, vcc
	global_store_dword v[2:3], v14, off
	global_store_dword v[2:3], v15, off offset:512
	global_store_dword v[2:3], v16, off offset:1024
	global_store_dword v[2:3], v17, off offset:1536
	s_and_saveexec_b64 s[88:89], s[22:23]
	s_cbranch_execz .LBB0_4208
	ds_read_b32 v4, v64 offset:252
	v_lshl_add_u64 v[2:3], s[24:25], 2, v[20:21]
	s_waitcnt lgkmcnt(0)
	v_mul_f32_e32 v4, 0x3fb8aa3b, v4
	v_exp_f32_e32 v4, v4
	global_store_dword v[2:3], v4, off
	s_branch .LBB0_4208

.LBB0_4229:
	v_mov_b32_e32 v18, v0
	s_add_i32 s2, s40, 0xffffff70
	v_readlane_b32 s48, v228, 34
	s_cmp_gt_u32 s2, 63
	v_readfirstlane_b32 s2, v18
	v_readlane_b32 s97, v228, 14
	v_readlane_b32 s49, v228, 35
	s_cbranch_scc1 .LBB0_4243
	s_lshl_b32 s5, s40, 4
	s_and_b32 s5, s5, 0xf00
	s_and_b32 s3, s40, 15
	s_addk_i32 s5, 0xf700
	s_lshl_b32 s7, s5, 4
	s_lshl_b32 s8, s3, 6
	s_or_b32 s7, s8, s7
	s_and_b32 s12, s7, 0x7fffe3c0
	v_ashrrev_i32_e32 v19, 6, v18
	s_lshr_b32 s6, s5, 7
	s_waitcnt lgkmcnt(0)
	v_add_u32_e32 v2, s12, v19
	s_movk_i32 s13, 0x3000
	v_mov_b64_e32 v[10:11], s[46:47]
	s_and_b32 s6, s6, 2
	s_mov_b32 s7, 0
	v_mad_i64_i32 v[2:3], s[8:9], v2, s13, v[10:11]
	v_add_u32_e32 v24, 0x200, v18
	v_and_b32_e32 v26, 63, v18
	s_lshl_b32 s8, s6, 8
	s_mov_b32 s9, s7
	v_ashrrev_i32_e32 v29, 6, v24
	v_mov_b32_e32 v23, 0
	v_lshl_add_u64 v[2:3], v[2:3], 0, s[8:9]
	v_lshlrev_b32_e32 v22, 2, v26
	v_add_u32_e32 v4, s12, v29
	v_add_u32_e32 v25, 0x400, v18
	v_lshl_add_u64 v[2:3], v[2:3], 0, v[22:23]
	s_movk_i32 s14, 0x1000
	v_mad_i64_i32 v[4:5], s[10:11], v4, s13, v[10:11]
	v_ashrrev_i32_e32 v33, 6, v25
	v_add_co_u32_e32 v2, vcc, s14, v2
	v_lshl_add_u64 v[4:5], v[4:5], 0, s[8:9]
	v_add_u32_e32 v6, s12, v33
	v_add_u32_e32 v43, 0x600, v18
	v_addc_co_u32_e32 v3, vcc, 0, v3, vcc
	v_lshl_add_u64 v[4:5], v[4:5], 0, v[22:23]
	v_mad_i64_i32 v[6:7], s[10:11], v6, s13, v[10:11]
	v_ashrrev_i32_e32 v30, 6, v43
	v_add_co_u32_e32 v4, vcc, s14, v4
	v_lshl_add_u64 v[6:7], v[6:7], 0, s[8:9]
	v_add_u32_e32 v8, s12, v30
	v_add_u32_e32 v12, 0x800, v18
	v_addc_co_u32_e32 v5, vcc, 0, v5, vcc
	v_lshl_add_u64 v[6:7], v[6:7], 0, v[22:23]
	v_mad_i64_i32 v[8:9], s[10:11], v8, s13, v[10:11]
	v_ashrrev_i32_e32 v32, 6, v12
	v_add_co_u32_e32 v6, vcc, s14, v6
	v_lshl_add_u64 v[8:9], v[8:9], 0, s[8:9]
	v_add_u32_e32 v12, s12, v32
	v_add_u32_e32 v14, 0xa00, v18
	v_addc_co_u32_e32 v7, vcc, 0, v7, vcc
	v_lshl_add_u64 v[8:9], v[8:9], 0, v[22:23]
	v_mad_i64_i32 v[12:13], s[10:11], v12, s13, v[10:11]
	v_ashrrev_i32_e32 v28, 6, v14
	v_add_co_u32_e32 v8, vcc, s14, v8
	v_lshl_add_u64 v[12:13], v[12:13], 0, s[8:9]
	v_add_u32_e32 v14, s12, v28
	v_add_u32_e32 v16, 0xc00, v18
	v_addc_co_u32_e32 v9, vcc, 0, v9, vcc
	v_lshl_add_u64 v[12:13], v[12:13], 0, v[22:23]
	v_mad_i64_i32 v[14:15], s[10:11], v14, s13, v[10:11]
	v_ashrrev_i32_e32 v31, 6, v16
	v_add_co_u32_e32 v12, vcc, s14, v12
	v_lshl_add_u64 v[14:15], v[14:15], 0, s[8:9]
	v_add_u32_e32 v16, s12, v31
	v_add_u32_e32 v20, 0xe00, v18
	v_addc_co_u32_e32 v13, vcc, 0, v13, vcc
	v_lshl_add_u64 v[14:15], v[14:15], 0, v[22:23]
	v_mad_i64_i32 v[16:17], s[10:11], v16, s13, v[10:11]
	v_ashrrev_i32_e32 v27, 6, v20
	v_add_co_u32_e32 v14, vcc, s14, v14
	v_lshl_add_u64 v[16:17], v[16:17], 0, s[8:9]
	v_add_u32_e32 v20, s12, v27
	v_addc_co_u32_e32 v15, vcc, 0, v15, vcc
	v_lshl_add_u64 v[16:17], v[16:17], 0, v[22:23]
	v_mad_i64_i32 v[20:21], s[10:11], v20, s13, v[10:11]
	v_add_co_u32_e32 v16, vcc, s14, v16
	v_lshl_add_u64 v[20:21], v[20:21], 0, s[8:9]
	s_nop 0
	v_addc_co_u32_e32 v17, vcc, 0, v17, vcc
	v_lshl_add_u64 v[20:21], v[20:21], 0, v[22:23]
	v_add_co_u32_e32 v20, vcc, s14, v20
	v_lshlrev_b32_e32 v35, 2, v18
	s_nop 0
	v_addc_co_u32_e32 v21, vcc, 0, v21, vcc
	global_load_dword v42, v[2:3], off offset:2144
	global_load_dword v41, v[4:5], off offset:2144
	global_load_dword v40, v[6:7], off offset:2144
	global_load_dword v39, v[8:9], off offset:2144
	global_load_dword v38, v[12:13], off offset:2144
	global_load_dword v37, v[14:15], off offset:2144
	global_load_dword v36, v[16:17], off offset:2144
	global_load_dword v34, v[20:21], off offset:2144
	v_ashrrev_i32_e32 v2, 5, v18
	v_add_u32_e32 v2, s12, v2
	v_and_b32_e32 v4, 0x7c, v35
	v_mad_i64_i32 v[2:3], s[8:9], v2, s13, v[10:11]
	s_lshl_b32 s8, s6, 9
	s_mov_b32 s9, s7
	v_lshlrev_b32_e32 v20, 2, v4
	v_ashrrev_i32_e32 v4, 5, v24
	v_lshl_add_u64 v[2:3], v[2:3], 0, s[8:9]
	v_mov_b32_e32 v21, v23
	v_add_u32_e32 v4, s12, v4
	v_lshl_add_u64 v[2:3], v[2:3], 0, v[20:21]
	v_mad_i64_i32 v[4:5], s[10:11], v4, s13, v[10:11]
	v_ashrrev_i32_e32 v12, 5, v25
	v_add_co_u32_e32 v2, vcc, s14, v2
	v_lshl_add_u64 v[4:5], v[4:5], 0, s[8:9]
	v_add_u32_e32 v12, s12, v12
	v_addc_co_u32_e32 v3, vcc, 0, v3, vcc
	v_lshl_add_u64 v[4:5], v[4:5], 0, v[20:21]
	v_mad_i64_i32 v[12:13], s[10:11], v12, s13, v[10:11]
	v_ashrrev_i32_e32 v14, 5, v43
	v_add_co_u32_e32 v6, vcc, s14, v4
	v_lshl_add_u64 v[12:13], v[12:13], 0, s[8:9]
	v_add_u32_e32 v14, s12, v14
	v_addc_co_u32_e32 v7, vcc, 0, v5, vcc
	v_lshl_add_u64 v[12:13], v[12:13], 0, v[20:21]
	v_mad_i64_i32 v[10:11], s[10:11], v14, s13, v[10:11]
	v_add_co_u32_e32 v12, vcc, s14, v12
	v_lshl_add_u64 v[10:11], v[10:11], 0, s[8:9]
	s_nop 0
	v_addc_co_u32_e32 v13, vcc, 0, v13, vcc
	v_lshl_add_u64 v[10:11], v[10:11], 0, v[20:21]
	v_add_co_u32_e32 v14, vcc, 0x1000, v10
	global_load_dwordx4 v[2:5], v[2:3], off offset:3168
	s_nop 0
	global_load_dwordx4 v[6:9], v[6:7], off offset:3168
	v_addc_co_u32_e32 v15, vcc, 0, v11, vcc
	global_load_dwordx4 v[10:13], v[12:13], off offset:3168
	s_nop 0
	global_load_dwordx4 v[14:17], v[14:15], off offset:3168
	s_movk_i32 s8, 0x400
	s_lshl_b32 s6, s6, 6
	v_cmp_gt_i32_e32 vcc, s8, v18
	s_waitcnt vmcnt(0) lgkmcnt(0)
	s_barrier
	s_and_saveexec_b64 s[8:9], vcc
	s_cbranch_execz .LBB0_4235
	v_and_b32_e32 v21, 15, v18
	v_readlane_b32 s10, v228, 31
	v_lshlrev_b32_e32 v24, 2, v21
	v_mov_b32_e32 v25, v23
	v_readlane_b32 s11, v228, 32
	s_movk_i32 s14, 0x1ff
	v_mov_b32_e32 v23, v18
	v_lshl_add_u64 v[24:25], s[10:11], 0, v[24:25]
	v_readlane_b32 s10, v228, 10
	s_nop 1
	v_lshl_add_u32 v21, v21, 8, s10
	s_mov_b64 s[10:11], 0
.LBB0_4232:
	v_ashrrev_i32_e32 v43, 4, v23
	v_add_u32_e32 v44, s12, v43
	v_mad_i64_i32 v[44:45], s[16:17], v44, s13, v[24:25]
	global_load_dword v44, v[44:45], off
	v_add_u32_e32 v45, 0x200, v23
	v_cmp_lt_i32_e32 vcc, s14, v23
	v_lshl_add_u32 v43, v43, 2, v21
	s_or_b64 s[10:11], vcc, s[10:11]
	v_mov_b32_e32 v23, v45
	s_waitcnt vmcnt(0) lgkmcnt(0)
	ds_write_b32 v43, v44
	s_andn2_b64 exec, exec, s[10:11]
	s_cbranch_execnz .LBB0_4232
	s_or_b64 exec, exec, s[10:11]
	v_add_u32_e32 v21, 0xfffffe00, v18
	s_mov_b64 s[10:11], 0
	v_mov_b64_e32 v[24:25], s[0:1]
	s_lshl_b32 s12, s6, 2
	s_mov_b32 s13, 0
	v_mov_b32_e32 v23, 0
	s_movk_i32 s14, 0x1ff
	v_mov_b32_e32 v43, v35
.LBB0_4234:
	global_load_dwordx2 v[44:45], v[24:25], off offset:152 sc0 sc1
	s_waitcnt vmcnt(0)
	v_and_b32_e32 v46, 0xffffff00, v43
	v_ashrrev_i32_e32 v47, 31, v46
	v_add_u32_e32 v21, 0x200, v21
	s_waitcnt lgkmcnt(0)
	v_lshl_add_u64 v[44:45], v[46:47], 2, v[44:45]
	v_lshl_add_u64 v[44:45], v[44:45], 0, s[12:13]
	v_lshl_add_u64 v[44:45], v[44:45], 0, v[22:23]
	v_add_co_u32_e32 v44, vcc, 0x4000, v44
	s_nop 1
	v_addc_co_u32_e32 v45, vcc, 0, v45, vcc
	global_load_dword v44, v[44:45], off
	v_cmp_lt_i32_e32 vcc, s14, v21
	v_add_u32_e32 v45, s4, v43
	v_add_u32_e32 v43, 0x800, v43
	s_or_b64 s[10:11], vcc, s[10:11]
	s_waitcnt vmcnt(0)
	ds_write_b32 v45, v44
	s_andn2_b64 exec, exec, s[10:11]
	s_cbranch_execnz .LBB0_4234

.LBB0_4237:
	global_load_dwordx2 v[44:45], v[24:25], off offset:160 sc0 sc1
	s_waitcnt vmcnt(0)
	v_ashrrev_i32_e32 v46, 6, v43
	v_ashrrev_i32_e32 v47, 31, v46
	v_lshl_add_u64 v[48:49], s[6:7], 0, v[46:47]
	v_add_u32_e32 v79, 0x200, v43
	v_cmp_lt_i32_e32 vcc, s15, v43
	v_lshl_add_u32 v43, v46, 2, s4
	v_mad_u64_u32 v[46:47], s[18:19], v46, s14, v[22:23]
	s_or_b64 s[10:11], vcc, s[10:11]
	s_waitcnt lgkmcnt(0)
	v_lshl_add_u64 v[44:45], v[48:49], 2, v[44:45]
	global_load_dword v78, v[44:45], off offset:1024
	ds_read2st64_b32 v[44:45], v21 offset1:1
	ds_read2st64_b32 v[48:49], v21 offset0:2 offset1:3
	ds_read2st64_b32 v[50:51], v21 offset0:4 offset1:5
	ds_read2st64_b32 v[52:53], v21 offset0:6 offset1:7
	ds_read2st64_b32 v[54:55], v21 offset0:8 offset1:9
	ds_read2st64_b32 v[56:57], v21 offset0:10 offset1:11
	ds_read2st64_b32 v[58:59], v21 offset0:12 offset1:13
	ds_read2st64_b32 v[60:61], v21 offset0:14 offset1:15
	ds_read2st64_b32 v[62:63], v43 offset1:1
	ds_read2st64_b32 v[64:65], v43 offset0:2 offset1:3
	ds_read2st64_b32 v[66:67], v43 offset0:4 offset1:5
	ds_read2st64_b32 v[68:69], v43 offset0:6 offset1:7
	ds_read2st64_b32 v[70:71], v43 offset0:8 offset1:9
	ds_read2st64_b32 v[72:73], v43 offset0:10 offset1:11
	ds_read2st64_b32 v[74:75], v43 offset0:12 offset1:13
	ds_read2st64_b32 v[76:77], v43 offset0:14 offset1:15
	s_waitcnt lgkmcnt(4)
	v_pk_mul_f32 v[52:53], v[52:53], v[68:69]
	s_waitcnt lgkmcnt(3)
	v_pk_mul_f32 v[54:55], v[54:55], v[70:71]
	s_waitcnt lgkmcnt(2)
	v_pk_mul_f32 v[56:57], v[56:57], v[72:73]
	s_waitcnt lgkmcnt(1)
	v_pk_mul_f32 v[58:59], v[58:59], v[74:75]
	s_waitcnt lgkmcnt(0)
	v_pk_mul_f32 v[60:61], v[60:61], v[76:77]
	s_waitcnt vmcnt(0)
	v_fmac_f32_e32 v78, v44, v62
	v_fmac_f32_e32 v78, v45, v63
	v_fmac_f32_e32 v78, v48, v64
	v_fmac_f32_e32 v78, v49, v65
	v_fmac_f32_e32 v78, v50, v66
	v_fmac_f32_e32 v78, v51, v67
	v_add_f32_e32 v43, v78, v52
	v_add_f32_e32 v43, v43, v53
	v_add_f32_e32 v43, v43, v54
	v_add_f32_e32 v43, v43, v55
	v_add_f32_e32 v43, v43, v56
	v_add_f32_e32 v43, v43, v57
	v_add_f32_e32 v43, v43, v58
	v_add_f32_e32 v43, v43, v59
	v_add_f32_e32 v43, v43, v60
	v_add_f32_e32 v44, v43, v61
	v_mul_f32_e64 v43, |v44|, s3
	v_exp_f32_e32 v45, v43
	v_min_f32_e32 v44, 0, v44
	v_mov_b32_e32 v43, v79
	v_add_f32_e32 v45, 1.0, v45
	v_cmp_gt_f32_e32 vcc, s5, v45
	s_nop 1
	v_cndmask_b32_e64 v47, 0, 32, vcc
	v_ldexp_f32 v45, v45, v47
	v_log_f32_e32 v45, v45
	v_cndmask_b32_e32 v47, 0, v23, vcc
	v_mul_f32_e32 v48, 0x3f317217, v45
	v_fma_f32 v48, v45, s12, -v48
	v_fmac_f32_e32 v48, 0x3377d1cf, v45
	v_fmac_f32_e32 v48, 0x3f317217, v45
	v_cmp_lt_f32_e64 vcc, |v45|, s13
	s_nop 1
	v_cndmask_b32_e32 v45, v45, v48, vcc
	v_sub_f32_e32 v45, v45, v47
	v_sub_f32_e32 v44, v44, v45
	v_mul_f32_e32 v44, 0x3d800000, v44
	ds_write_b32 v46, v44
	s_andn2_b64 exec, exec, s[10:11]
	s_cbranch_execnz .LBB0_4237
.LBB0_4238:
	s_or_b64 exec, exec, s[8:9]
	s_ashr_i32 s3, s2, 6
	s_mul_i32 s4, s3, 0x820
	s_add_i32 s4, s4, s94
	v_lshl_add_u32 v24, v26, 2, s4
	s_waitcnt lgkmcnt(0)
	s_barrier
	ds_read2_b32 v[22:23], v24 offset1:65
	v_and_b32_e32 v21, 64, v1
	v_add_u32_e32 v25, -1, v1
	v_cmp_lt_i32_e32 vcc, v25, v21
	v_subrev_u32_e32 v49, 32, v1
	v_cmp_lt_i32_e64 s[14:15], v49, v21
	v_cndmask_b32_e32 v25, v25, v1, vcc
	v_lshlrev_b32_e32 v25, 2, v25
	s_waitcnt lgkmcnt(0)
	ds_bpermute_b32 v43, v25, v22
	v_cmp_eq_u32_e32 vcc, 0, v26
	ds_bpermute_b32 v47, v25, v23
	s_movk_i32 s4, 0x104
	s_mov_b32 s17, 0
	s_waitcnt lgkmcnt(1)
	v_add_f32_e32 v43, v22, v43
	v_cndmask_b32_e32 v22, v43, v22, vcc
	v_add_u32_e32 v43, -2, v1
	v_cmp_lt_i32_e64 s[6:7], v43, v21
	s_waitcnt lgkmcnt(0)
	v_add_f32_e32 v47, v23, v47
	v_cndmask_b32_e32 v23, v47, v23, vcc
	v_cndmask_b32_e64 v43, v43, v1, s[6:7]
	v_lshlrev_b32_e32 v43, 2, v43
	ds_bpermute_b32 v44, v43, v22
	v_cmp_gt_u32_e64 s[6:7], 2, v26
	ds_bpermute_b32 v47, v43, v23
	s_and_b32 s3, s3, 3
	s_ashr_i32 s2, s2, 8
	s_waitcnt lgkmcnt(1)
	v_add_f32_e32 v44, v22, v44
	v_cndmask_b32_e64 v22, v44, v22, s[6:7]
	v_add_u32_e32 v44, -4, v1
	v_cmp_lt_i32_e64 s[8:9], v44, v21
	s_waitcnt lgkmcnt(0)
	v_add_f32_e32 v47, v23, v47
	v_cndmask_b32_e64 v23, v47, v23, s[6:7]
	v_cndmask_b32_e64 v44, v44, v1, s[8:9]
	v_lshlrev_b32_e32 v44, 2, v44
	ds_bpermute_b32 v45, v44, v22
	v_cmp_gt_u32_e64 s[8:9], 4, v26
	ds_bpermute_b32 v47, v44, v23
	s_waitcnt lgkmcnt(1)
	v_add_f32_e32 v45, v22, v45
	v_cndmask_b32_e64 v22, v45, v22, s[8:9]
	v_add_u32_e32 v45, -8, v1
	v_cmp_lt_i32_e64 s[10:11], v45, v21
	s_nop 1
	v_cndmask_b32_e64 v45, v45, v1, s[10:11]
	v_lshlrev_b32_e32 v45, 2, v45
	ds_bpermute_b32 v46, v45, v22
	v_cmp_gt_u32_e64 s[10:11], 8, v26
	s_waitcnt lgkmcnt(0)
	v_add_f32_e32 v46, v22, v46
	v_cndmask_b32_e64 v22, v46, v22, s[10:11]
	v_add_u32_e32 v46, -16, v1
	v_cmp_lt_i32_e64 s[12:13], v46, v21
	v_cndmask_b32_e64 v21, v49, v1, s[14:15]
	v_lshlrev_b32_e32 v21, 2, v21
	v_cndmask_b32_e64 v46, v46, v1, s[12:13]
	v_lshlrev_b32_e32 v46, 2, v46
	ds_bpermute_b32 v48, v46, v22
	v_cmp_gt_u32_e64 s[12:13], 16, v26
	v_cmp_gt_u32_e64 s[14:15], 32, v26
	s_waitcnt lgkmcnt(0)
	v_add_f32_e32 v48, v22, v48
	v_cndmask_b32_e64 v48, v48, v22, s[12:13]
	v_add_f32_e32 v22, v23, v47
	v_cndmask_b32_e64 v47, v22, v23, s[8:9]
	ds_read2_b32 v[22:23], v24 offset0:130 offset1:195
	ds_bpermute_b32 v50, v45, v47
	ds_bpermute_b32 v51, v21, v48
	s_waitcnt lgkmcnt(2)
	ds_bpermute_b32 v49, v25, v22
	s_waitcnt lgkmcnt(2)
	v_add_f32_e32 v50, v47, v50
	v_cndmask_b32_e64 v47, v50, v47, s[10:11]
	ds_bpermute_b32 v50, v46, v47
	s_waitcnt lgkmcnt(2)
	v_add_f32_e32 v51, v48, v51
	s_waitcnt lgkmcnt(1)
	v_add_f32_e32 v49, v22, v49
	v_cndmask_b32_e32 v22, v49, v22, vcc
	ds_bpermute_b32 v49, v43, v22
	s_waitcnt lgkmcnt(1)
	v_add_f32_e32 v50, v47, v50
	v_cndmask_b32_e64 v47, v50, v47, s[12:13]
	ds_bpermute_b32 v50, v21, v47
	v_cndmask_b32_e64 v48, v51, v48, s[14:15]
	s_waitcnt lgkmcnt(1)
	v_add_f32_e32 v49, v22, v49
	v_cndmask_b32_e64 v22, v49, v22, s[6:7]
	ds_bpermute_b32 v49, v44, v22
	ds_bpermute_b32 v51, v25, v23
	s_waitcnt lgkmcnt(2)
	v_add_f32_e32 v50, v47, v50
	v_cndmask_b32_e64 v47, v50, v47, s[14:15]
	ds_write2_b32 v24, v48, v47 offset1:65
	s_waitcnt lgkmcnt(2)
	v_add_f32_e32 v49, v22, v49
	v_cndmask_b32_e64 v22, v49, v22, s[8:9]
	s_waitcnt lgkmcnt(1)
	v_add_f32_e32 v50, v23, v51
	ds_bpermute_b32 v49, v45, v22
	v_cndmask_b32_e32 v23, v50, v23, vcc
	ds_bpermute_b32 v50, v43, v23
	s_waitcnt lgkmcnt(1)
	v_add_f32_e32 v47, v22, v49
	v_cndmask_b32_e64 v47, v47, v22, s[10:11]
	s_waitcnt lgkmcnt(0)
	v_add_f32_e32 v22, v23, v50
	v_cndmask_b32_e64 v49, v22, v23, s[6:7]
	v_add_u32_e32 v50, 0x400, v24
	ds_read2_b32 v[22:23], v50 offset0:4 offset1:69
	ds_bpermute_b32 v51, v44, v49
	ds_bpermute_b32 v48, v46, v47
	s_waitcnt lgkmcnt(2)
	ds_bpermute_b32 v52, v25, v22
	s_waitcnt lgkmcnt(2)
	v_add_f32_e32 v51, v49, v51
	v_cndmask_b32_e64 v49, v51, v49, s[8:9]
	ds_bpermute_b32 v51, v45, v49
	s_waitcnt lgkmcnt(2)
	v_add_f32_e32 v48, v47, v48
	v_cndmask_b32_e64 v47, v48, v47, s[12:13]
	s_waitcnt lgkmcnt(1)
	v_add_f32_e32 v52, v22, v52
	ds_bpermute_b32 v48, v21, v47
	v_cndmask_b32_e32 v22, v52, v22, vcc
	ds_bpermute_b32 v52, v43, v22
	s_waitcnt lgkmcnt(2)
	v_add_f32_e32 v51, v49, v51
	v_cndmask_b32_e64 v49, v51, v49, s[10:11]
	ds_bpermute_b32 v51, v46, v49
	s_waitcnt lgkmcnt(2)
	v_add_f32_e32 v48, v47, v48
	v_cndmask_b32_e64 v47, v48, v47, s[14:15]
	s_waitcnt lgkmcnt(1)
	v_add_f32_e32 v48, v22, v52
	v_cndmask_b32_e64 v22, v48, v22, s[6:7]
	ds_bpermute_b32 v48, v44, v22
	s_waitcnt lgkmcnt(1)
	v_add_f32_e32 v51, v49, v51
	v_cndmask_b32_e64 v49, v51, v49, s[12:13]
	ds_bpermute_b32 v51, v25, v23
	ds_bpermute_b32 v52, v21, v49
	s_waitcnt lgkmcnt(2)
	v_add_f32_e32 v48, v22, v48
	v_cndmask_b32_e64 v22, v48, v22, s[8:9]
	ds_bpermute_b32 v48, v45, v22
	s_waitcnt lgkmcnt(2)
	v_add_f32_e32 v51, v23, v51
	v_cndmask_b32_e32 v23, v51, v23, vcc
	ds_bpermute_b32 v51, v43, v23
	s_waitcnt lgkmcnt(2)
	v_add_f32_e32 v52, v49, v52
	s_waitcnt lgkmcnt(1)
	v_add_f32_e32 v48, v22, v48
	v_cndmask_b32_e64 v22, v48, v22, s[10:11]
	ds_bpermute_b32 v48, v46, v22
	s_waitcnt lgkmcnt(1)
	v_add_f32_e32 v51, v23, v51
	v_cndmask_b32_e64 v23, v51, v23, s[6:7]
	ds_bpermute_b32 v51, v44, v23
	v_cndmask_b32_e64 v49, v52, v49, s[14:15]
	s_waitcnt lgkmcnt(1)
	v_add_f32_e32 v48, v22, v48
	v_cndmask_b32_e64 v48, v48, v22, s[12:13]
	ds_write2_b32 v24, v47, v49 offset0:130 offset1:195
	s_waitcnt lgkmcnt(1)
	v_add_f32_e32 v22, v23, v51
	v_cndmask_b32_e64 v51, v22, v23, s[8:9]
	ds_read2_b32 v[22:23], v50 offset0:134 offset1:199
	ds_bpermute_b32 v52, v21, v48
	ds_bpermute_b32 v53, v45, v51
	s_waitcnt lgkmcnt(2)
	ds_bpermute_b32 v47, v25, v22
	ds_bpermute_b32 v25, v25, v23
	s_waitcnt lgkmcnt(3)
	v_add_f32_e32 v24, v48, v52
	v_cndmask_b32_e64 v24, v24, v48, s[14:15]
	s_waitcnt lgkmcnt(2)
	v_add_f32_e32 v48, v51, v53
	s_waitcnt lgkmcnt(1)
	v_add_f32_e32 v47, v22, v47
	s_waitcnt lgkmcnt(0)
	v_add_f32_e32 v25, v23, v25
	v_cndmask_b32_e32 v22, v47, v22, vcc
	v_cndmask_b32_e32 v23, v25, v23, vcc
	ds_bpermute_b32 v47, v43, v22
	ds_bpermute_b32 v25, v43, v23
	v_cndmask_b32_e64 v48, v48, v51, s[10:11]
	ds_bpermute_b32 v49, v46, v48
	s_waitcnt lgkmcnt(2)
	v_add_f32_e32 v47, v22, v47
	s_waitcnt lgkmcnt(1)
	v_add_f32_e32 v25, v23, v25
	v_cndmask_b32_e64 v22, v47, v22, s[6:7]
	v_cndmask_b32_e64 v23, v25, v23, s[6:7]
	ds_bpermute_b32 v47, v44, v22
	ds_bpermute_b32 v25, v44, v23
	s_waitcnt lgkmcnt(2)
	v_add_f32_e32 v43, v48, v49
	v_cndmask_b32_e64 v43, v43, v48, s[12:13]
	v_readlane_b32 s6, v228, 8
	s_waitcnt lgkmcnt(1)
	v_add_f32_e32 v44, v22, v47
	s_waitcnt lgkmcnt(0)
	v_add_f32_e32 v25, v23, v25
	v_cndmask_b32_e64 v22, v44, v22, s[8:9]
	v_cndmask_b32_e64 v23, v25, v23, s[8:9]
	ds_bpermute_b32 v44, v45, v22
	ds_bpermute_b32 v25, v45, v23
	ds_bpermute_b32 v45, v21, v43
	v_readlane_b32 s7, v228, 9
	s_waitcnt lgkmcnt(2)
	v_add_f32_e32 v44, v22, v44
	s_waitcnt lgkmcnt(1)
	v_add_f32_e32 v25, v23, v25
	v_cndmask_b32_e64 v22, v44, v22, s[10:11]
	v_cndmask_b32_e64 v23, v25, v23, s[10:11]
	ds_bpermute_b32 v44, v46, v22
	ds_bpermute_b32 v25, v46, v23
	s_waitcnt lgkmcnt(2)
	v_add_f32_e32 v45, v43, v45
	s_waitcnt lgkmcnt(1)
	v_add_f32_e32 v44, v22, v44
	s_waitcnt lgkmcnt(0)
	v_add_f32_e32 v25, v23, v25
	v_cndmask_b32_e64 v22, v44, v22, s[12:13]
	v_cndmask_b32_e64 v23, v25, v23, s[12:13]
	ds_bpermute_b32 v44, v21, v22
	ds_bpermute_b32 v21, v21, v23
	v_cndmask_b32_e64 v25, v45, v43, s[14:15]
	ds_write2_b32 v50, v24, v25 offset0:4 offset1:69
	s_waitcnt lgkmcnt(2)
	v_add_f32_e32 v24, v22, v44
	s_waitcnt lgkmcnt(1)
	v_add_f32_e32 v21, v23, v21
	v_cndmask_b32_e64 v22, v24, v22, s[14:15]
	v_cndmask_b32_e64 v21, v21, v23, s[14:15]
	ds_write2_b32 v50, v22, v21 offset0:134 offset1:199
	v_mov_b32_e32 v21, s94
	v_mad_u32_u24 v21, v26, s4, v21
	v_lshl_add_u32 v19, v19, 2, v21
	s_waitcnt lgkmcnt(0)
	s_barrier
	ds_read_b32 v24, v19
	ds_read_b32 v19, v21 offset:252
	s_lshl_b64 s[4:5], s[16:17], 14
	s_add_u32 s4, s6, s4
	s_addc_u32 s5, s7, s5
	v_lshl_add_u32 v28, v28, 2, v21
	s_waitcnt lgkmcnt(0)
	v_sub_f32_e32 v19, v19, v24
	v_mul_f32_e32 v19, 0x3fb8aa3b, v19
	v_exp_f32_e32 v19, v19
	s_lshl_b32 s3, s3, 7
	v_mul_f32_e32 v22, v42, v19
	v_ashrrev_i32_e32 v19, 31, v18
	v_lshl_add_u32 v42, v18, 2, s94
	ds_write_b32 v42, v22 offset:16640
	v_lshl_add_u64 v[22:23], v[18:19], 2, s[4:5]
	global_store_dword v[22:23], v24, off
	v_lshl_add_u32 v24, v29, 2, v21
	ds_read_b32 v24, v24
	ds_read_b32 v25, v21 offset:252
	s_movk_i32 s4, 0x1000
	s_waitcnt lgkmcnt(0)
	v_sub_f32_e32 v25, v25, v24
	v_mul_f32_e32 v25, 0x3fb8aa3b, v25
	v_exp_f32_e32 v25, v25
	s_nop 0
	v_mul_f32_e32 v25, v41, v25
	ds_write_b32 v42, v25 offset:18688
	global_store_dword v[22:23], v24, off offset:2048
	v_lshl_add_u32 v24, v33, 2, v21
	ds_read_b32 v29, v24
	ds_read_b32 v24, v21 offset:252
	s_waitcnt lgkmcnt(0)
	v_sub_f32_e32 v24, v24, v29
	v_mul_f32_e32 v24, 0x3fb8aa3b, v24
	v_exp_f32_e32 v24, v24
	s_nop 0
	v_mul_f32_e32 v24, v40, v24
	ds_write_b32 v42, v24 offset:20736
	v_add_co_u32_e32 v24, vcc, s4, v22
	s_movk_i32 s4, 0x2000
	s_nop 0
	v_addc_co_u32_e32 v25, vcc, 0, v23, vcc
	global_store_dword v[24:25], v29, off
	v_lshl_add_u32 v29, v30, 2, v21
	ds_read_b32 v29, v29
	ds_read_b32 v30, v21 offset:252
	s_waitcnt lgkmcnt(0)
	v_sub_f32_e32 v30, v30, v29
	v_mul_f32_e32 v30, 0x3fb8aa3b, v30
	v_exp_f32_e32 v30, v30
	s_nop 0
	v_mul_f32_e32 v30, v39, v30
	ds_write_b32 v42, v30 offset:22784
	global_store_dword v[24:25], v29, off offset:2048
	v_lshl_add_u32 v24, v32, 2, v21
	ds_read_b32 v29, v24
	ds_read_b32 v24, v21 offset:252
	s_waitcnt lgkmcnt(0)
	v_sub_f32_e32 v24, v24, v29
	v_mul_f32_e32 v24, 0x3fb8aa3b, v24
	v_exp_f32_e32 v24, v24
	s_nop 0
	v_mul_f32_e32 v24, v38, v24
	ds_write_b32 v42, v24 offset:24832
	v_add_co_u32_e32 v24, vcc, s4, v22
	s_movk_i32 s4, 0x3000
	s_nop 0
	v_addc_co_u32_e32 v25, vcc, 0, v23, vcc
	global_store_dword v[24:25], v29, off
	ds_read_b32 v28, v28
	ds_read_b32 v29, v21 offset:252
	s_waitcnt lgkmcnt(0)
	v_sub_f32_e32 v29, v29, v28
	v_mul_f32_e32 v29, 0x3fb8aa3b, v29
	v_exp_f32_e32 v29, v29
	s_nop 0
	v_mul_f32_e32 v29, v37, v29
	ds_write_b32 v42, v29 offset:26880
	global_store_dword v[24:25], v28, off offset:2048
	v_lshl_add_u32 v24, v31, 2, v21
	ds_read_b32 v28, v24
	ds_read_b32 v24, v21 offset:252
	s_waitcnt lgkmcnt(0)
	v_sub_f32_e32 v24, v24, v28
	v_mul_f32_e32 v24, 0x3fb8aa3b, v24
	v_exp_f32_e32 v24, v24
	s_nop 0
	v_mul_f32_e32 v24, v36, v24
	ds_write_b32 v42, v24 offset:28928
	v_add_co_u32_e32 v24, vcc, s4, v22
	v_lshl_add_u32 v22, v27, 2, v21
	s_nop 0
	v_addc_co_u32_e32 v25, vcc, 0, v23, vcc
	global_store_dword v[24:25], v28, off
	ds_read_b32 v23, v22
	ds_read_b32 v21, v21 offset:252
	v_lshrrev_b32_e32 v22, 5, v26
	v_and_b32_e32 v26, 31, v18
	s_lshl_b32 s4, s2, 7
	s_waitcnt lgkmcnt(0)
	v_sub_f32_e32 v21, v21, v23
	v_mul_f32_e32 v21, 0x3fb8aa3b, v21
	v_exp_f32_e32 v21, v21
	s_nop 0
	v_mul_f32_e32 v21, v34, v21
	ds_write_b32 v42, v21 offset:30976
	v_and_b32_e32 v21, 0x3fffff80, v35
	v_lshlrev_b32_e32 v21, 2, v21
	v_add3_u32 v20, s94, v21, v20
	global_store_dword v[24:25], v23, off offset:2048
	ds_write_b128 v20, v[2:5] offset:33024
	ds_write_b128 v20, v[6:9] offset:41216
	ds_write_b128 v20, v[10:13] offset:49408
	ds_write_b128 v20, v[14:17] offset:57600
	v_lshlrev_b32_e32 v2, 9, v22
	v_lshlrev_b32_e32 v20, 2, v26
	v_or3_b32 v2, v2, s3, v20
	v_add_u32_e32 v2, s94, v2
	v_add_u32_e32 v21, 0x8100, v2
	v_lshl_add_u32 v2, v22, 8, s4
	v_or_b32_e32 v2, v2, v20
	v_add_u32_e32 v2, s94, v2
	v_add_u32_e32 v23, 0x4100, v2
	v_mov_b32_e32 v2, 0
	s_mov_b32 s4, s17
	v_mov_b32_e32 v3, v2
	v_mov_b32_e32 v4, v2
	v_mov_b32_e32 v5, v2
	v_mov_b32_e32 v6, v2
	v_mov_b32_e32 v7, v2
	v_mov_b32_e32 v8, v2
	v_mov_b32_e32 v9, v2
	v_mov_b32_e32 v10, v2
	v_mov_b32_e32 v11, v2
	v_mov_b32_e32 v12, v2
	v_mov_b32_e32 v13, v2
	v_mov_b32_e32 v14, v2
	v_mov_b32_e32 v15, v2
	v_mov_b32_e32 v16, v2
	v_mov_b32_e32 v17, v2
	s_waitcnt lgkmcnt(0)
	s_barrier
.LBB0_4239:
	v_add_u32_e32 v28, s4, v23
	ds_read2st64_b32 v[24:25], v28 offset1:2
	ds_read2st64_b32 v[26:27], v21 offset1:4
	s_addk_i32 s4, 0x1000
	s_cmpk_lg_i32 s4, 0x4000
	s_waitcnt lgkmcnt(0)
	v_mfma_f32_32x32x2_f32 v[2:17], v24, v26, v[2:17]
	v_mfma_f32_32x32x2_f32 v[2:17], v25, v27, v[2:17]
	ds_read2st64_b32 v[24:25], v28 offset0:4 offset1:6
	ds_read2st64_b32 v[26:27], v21 offset0:8 offset1:12
	s_waitcnt lgkmcnt(0)
	v_mfma_f32_32x32x2_f32 v[2:17], v24, v26, v[2:17]
	v_mfma_f32_32x32x2_f32 v[2:17], v25, v27, v[2:17]
	ds_read2st64_b32 v[24:25], v28 offset0:8 offset1:10
	ds_read2st64_b32 v[26:27], v21 offset0:16 offset1:20
	s_waitcnt lgkmcnt(0)
	v_mfma_f32_32x32x2_f32 v[2:17], v24, v26, v[2:17]
	v_mfma_f32_32x32x2_f32 v[2:17], v25, v27, v[2:17]
	ds_read2st64_b32 v[24:25], v28 offset0:12 offset1:14
	ds_read2st64_b32 v[26:27], v21 offset0:24 offset1:28
	v_add_u32_e32 v21, 0x2000, v21
	s_waitcnt lgkmcnt(0)
	v_mfma_f32_32x32x2_f32 v[2:17], v24, v26, v[2:17]
	v_mfma_f32_32x32x2_f32 v[2:17], v25, v27, v[2:17]
	s_cbranch_scc1 .LBB0_4239
	s_lshl_b32 s2, s2, 5
	s_lshl_b64 s[6:7], s[16:17], 6
	s_ashr_i32 s5, s2, 31
	s_add_u32 s4, s6, s2
	s_addc_u32 s5, s7, s5
	s_lshl_b64 s[4:5], s[4:5], 9
	v_readlane_b32 s2, v228, 22
	s_add_u32 s2, s2, s4
	v_readlane_b32 s4, v228, 12
	s_addc_u32 s4, s4, s5
	s_add_u32 s2, s2, s3
	s_addc_u32 s3, s4, 0
	v_mov_b32_e32 v21, 0
	v_lshl_add_u64 v[24:25], s[2:3], 0, v[20:21]
	v_lshlrev_b32_e32 v20, 11, v22
	v_lshl_add_u64 v[20:21], v[24:25], 0, v[20:21]
	s_movk_i32 s2, 0x1000
	global_store_dword v[20:21], v2, off
	global_store_dword v[20:21], v3, off offset:512
	global_store_dword v[20:21], v4, off offset:1024
	global_store_dword v[20:21], v5, off offset:1536
	v_add_co_u32_e32 v2, vcc, s2, v20
	s_movk_i32 s2, 0x2000
	s_nop 0
	v_addc_co_u32_e32 v3, vcc, 0, v21, vcc
	global_store_dword v[2:3], v6, off
	global_store_dword v[2:3], v7, off offset:512
	global_store_dword v[2:3], v8, off offset:1024
	global_store_dword v[2:3], v9, off offset:1536
	v_add_co_u32_e32 v2, vcc, s2, v20
	s_nop 1
	v_addc_co_u32_e32 v3, vcc, 0, v21, vcc
	global_store_dword v[2:3], v10, off
	global_store_dword v[2:3], v11, off offset:512
	global_store_dword v[2:3], v12, off offset:1024
	global_store_dword v[2:3], v13, off offset:1536
	v_add_co_u32_e32 v2, vcc, 0x3000, v20
	s_nop 1
	v_addc_co_u32_e32 v3, vcc, 0, v21, vcc
	v_cmp_gt_i32_e32 vcc, 64, v18
	global_store_dword v[2:3], v14, off
	global_store_dword v[2:3], v15, off offset:512
	global_store_dword v[2:3], v16, off offset:1024
	global_store_dword v[2:3], v17, off offset:1536
	s_and_saveexec_b64 s[8:9], vcc
	s_cbranch_execz .LBB0_4242
	s_movk_i32 s2, 0x104
	v_mul_lo_u32 v2, v18, s2
	v_add_u32_e32 v2, s94, v2
	ds_read_b32 v2, v2 offset:252
	s_lshl_b64 s[2:3], s[6:7], 2
	v_readlane_b32 s4, v228, 27
	v_readlane_b32 s5, v228, 28
	s_add_u32 s2, s4, s2
	s_waitcnt lgkmcnt(0)
	v_mul_f32_e32 v2, 0x3fb8aa3b, v2
	v_exp_f32_e32 v4, v2
	s_addc_u32 s3, s5, s3
	v_lshl_add_u64 v[2:3], v[18:19], 2, s[2:3]
	global_store_dword v[2:3], v4, off

.LBB0_4247:
	s_lshr_b32 s16, s2, 2
	s_add_i32 s18, s16, 0x4000
	s_mul_i32 s17, s18, 0x3000
	s_mul_hi_u32 s16, s18, 0x3000
	s_add_u32 s22, s46, s17
	s_addc_u32 s23, s47, s16
	s_waitcnt vmcnt(0)
	s_barrier
	s_and_saveexec_b64 s[16:17], s[6:7]
	s_xor_b64 s[16:17], exec, s[16:17]
	s_cbranch_execz .LBB0_4251
	s_and_saveexec_b64 s[24:25], s[10:11]
	s_cbranch_execz .LBB0_4250
	v_lshl_add_u64 v[42:43], v[4:5], 2, s[22:23]
	global_load_dword v42, v[42:43], off
	s_waitcnt vmcnt(0) lgkmcnt(0)
	ds_write_b32 v6, v42 offset:33280

.LBB0_4251:
	s_andn2_saveexec_b64 s[24:25], s[16:17]
	s_cbranch_execz .LBB0_4255
	v_mov_b64_e32 v[42:43], s[0:1]
	global_load_dwordx2 v[58:59], v[42:43], off offset:152 sc0 sc1
	s_waitcnt vmcnt(0)
	global_load_dwordx2 v[60:61], v[42:43], off offset:160 sc0 sc1
	s_waitcnt vmcnt(0)
	v_mov_b32_e32 v46, s22
	v_mov_b32_e32 v47, s23
	v_add_co_u32_e32 v54, vcc, 0x2000, v46
	v_lshl_add_u64 v[42:43], v[8:9], 2, s[22:23]
	v_lshl_add_u64 v[44:45], v[10:11], 2, s[22:23]
	v_addc_co_u32_e32 v55, vcc, 0, v47, vcc
	global_load_dword v66, v[42:43], off
	global_load_dword v67, v[44:45], off
	s_nop 0
	global_load_dwordx4 v[42:45], v[54:55], off offset:1120
	global_load_dwordx4 v[46:49], v[54:55], off offset:1136
	global_load_dwordx4 v[50:53], v[54:55], off offset:1152
	s_nop 0
	global_load_dwordx4 v[54:57], v[54:55], off offset:1168
	s_mov_b32 s21, s19
	s_waitcnt lgkmcnt(0)
	v_lshl_add_u64 v[58:59], v[58:59], 0, s[20:21]
	v_lshl_add_u64 v[60:61], v[16:17], 2, v[60:61]
	global_load_dword v68, v[60:61], off offset:1024
	v_lshl_add_u64 v[58:59], v[130:131], 2, v[58:59]
	v_add_co_u32_e32 v60, vcc, s28, v58
	v_add_co_u32_e64 v62, s[16:17], s30, v58
	s_nop 0
	v_addc_co_u32_e32 v61, vcc, 0, v59, vcc
	v_addc_co_u32_e64 v63, s[16:17], 0, v59, s[16:17]
	v_add_co_u32_e64 v64, s[16:17], s31, v58
	v_add_co_u32_e32 v58, vcc, s29, v58
	s_nop 0
	v_addc_co_u32_e64 v65, s[16:17], 0, v59, s[16:17]
	v_addc_co_u32_e32 v59, vcc, 0, v59, vcc
	global_load_dword v69, v[58:59], off offset:-4096
	global_load_dword v70, v[60:61], off offset:1024
	global_load_dword v71, v[60:61], off offset:2048
	s_nop 0
	global_load_dword v60, v[60:61], off offset:3072
	s_nop 0
	global_load_dword v61, v[58:59], off
	global_load_dword v72, v[58:59], off offset:1024
	global_load_dword v73, v[58:59], off offset:2048
	s_nop 0
	global_load_dword v58, v[58:59], off offset:3072
	s_nop 0
	global_load_dword v59, v[64:65], off offset:-4096
	global_load_dword v74, v[62:63], off offset:1024
	global_load_dword v75, v[62:63], off offset:2048
	s_nop 0
	global_load_dword v62, v[62:63], off offset:3072
	s_nop 0
	global_load_dword v63, v[64:65], off
	global_load_dword v76, v[64:65], off offset:1024
	global_load_dword v77, v[64:65], off offset:2048
	s_nop 0
	global_load_dword v64, v[64:65], off offset:3072
	v_cmp_lt_i32_e32 vcc, v36, v35
	s_waitcnt vmcnt(0)
	v_mul_f32_e32 v66, 0x3e000000, v66
	v_mul_f32_e32 v78, v66, v67
	v_cndmask_b32_e32 v65, v1, v36, vcc
	v_lshlrev_b32_e32 v65, 2, v65
	ds_bpermute_b32 v65, v65, v78
	v_cmp_lt_i32_e32 vcc, v37, v35
	s_waitcnt lgkmcnt(0)
	v_fmac_f32_e32 v65, v66, v67
	v_cndmask_b32_e32 v78, v1, v37, vcc
	v_lshlrev_b32_e32 v78, 2, v78
	ds_bpermute_b32 v78, v78, v65
	v_cmp_lt_i32_e32 vcc, v38, v35
	s_waitcnt lgkmcnt(0)
	v_add_f32_e32 v65, v65, v78
	v_cndmask_b32_e32 v79, v1, v38, vcc
	v_cmp_lt_i32_e32 vcc, v39, v35
	v_lshlrev_b32_e32 v79, 2, v79
	ds_bpermute_b32 v78, v79, v65
	v_cndmask_b32_e32 v80, v1, v39, vcc
	v_cmp_lt_i32_e32 vcc, v40, v35
	v_lshlrev_b32_e32 v80, 2, v80
	s_waitcnt lgkmcnt(0)
	v_add_f32_e32 v65, v65, v78
	v_cndmask_b32_e32 v79, v1, v40, vcc
	v_cmp_lt_i32_e32 vcc, v41, v35
	ds_bpermute_b32 v78, v80, v65
	v_fmac_f32_e32 v68, v42, v69
	v_fmac_f32_e32 v68, v43, v70
	v_fmac_f32_e32 v68, v44, v71
	v_fmac_f32_e32 v68, v45, v60
	v_fmac_f32_e32 v68, v46, v61
	v_fmac_f32_e32 v68, v47, v72
	v_fmac_f32_e32 v68, v48, v73
	v_fmac_f32_e32 v68, v49, v58
	v_fmac_f32_e32 v68, v50, v59
	v_fmac_f32_e32 v68, v51, v74
	v_fmac_f32_e32 v68, v52, v75
	v_fmac_f32_e32 v68, v53, v62
	v_fmac_f32_e32 v68, v54, v63
	v_fmac_f32_e32 v68, v55, v76
	v_fmac_f32_e32 v68, v56, v77
	v_fmac_f32_e32 v68, v57, v64
	v_mul_f32_e64 v42, |v68|, s33
	v_exp_f32_e32 v42, v42
	v_cndmask_b32_e32 v81, v1, v41, vcc
	v_lshlrev_b32_e32 v43, 2, v79
	s_waitcnt lgkmcnt(0)
	v_add_f32_e32 v45, v65, v78
	v_add_f32_e32 v42, 1.0, v42
	v_cmp_gt_f32_e32 vcc, s34, v42
	ds_bpermute_b32 v43, v43, v45
	v_lshlrev_b32_e32 v44, 2, v81
	v_cndmask_b32_e64 v46, 0, 32, vcc
	v_ldexp_f32 v42, v42, v46
	v_log_f32_e32 v42, v42
	v_cndmask_b32_e32 v47, 0, v34, vcc
	v_min_f32_e32 v46, 0, v68
	v_mul_f32_e32 v48, 0x3f317217, v42
	v_fma_f32 v48, v42, s35, -v48
	v_fmac_f32_e32 v48, 0x3377d1cf, v42
	v_fmac_f32_e32 v48, 0x3f317217, v42
	v_cmp_lt_f32_e64 vcc, |v42|, s36
	s_nop 1
	v_cndmask_b32_e32 v42, v42, v48, vcc
	v_sub_f32_e32 v42, v42, v47
	v_sub_f32_e32 v42, v46, v42
	v_mul_f32_e32 v42, 0x3d800000, v42
	v_mul_f32_e32 v42, 0x3fb8aa3b, v42
	v_exp_f32_e32 v46, v42
	s_waitcnt lgkmcnt(0)
	v_add_f32_e32 v42, v45, v43
	ds_bpermute_b32 v43, v44, v42
	v_mul_f32_e32 v44, v66, v46
	ds_write2st64_b32 v6, v44, v67 offset0:128 offset1:129
	ds_write_b32 v6, v46 offset:33280
	s_and_saveexec_b64 s[16:17], s[12:13]
	s_cbranch_execz .LBB0_4254
	s_waitcnt lgkmcnt(2)
	v_add_f32_e32 v42, v42, v43
	v_mov_b32_e32 v43, s94
	ds_write_b32 v43, v42 offset:34048

.LBB0_4255:
	s_or_b64 exec, exec, s[24:25]
	s_waitcnt lgkmcnt(0)
	v_mov_b64_e32 v[42:43], s[0:1]
	s_waitcnt lgkmcnt(0)
	s_barrier
	global_load_dwordx2 v[42:43], v[42:43], off offset:56 sc0 sc1
	s_waitcnt vmcnt(0)
	s_and_b32 s16, s2, 0x7ffffffc
	s_mov_b32 s17, s19
	s_add_i32 s16, s3, s16
	s_lshl_b64 s[16:17], s[16:17], 15
	s_waitcnt lgkmcnt(0)
	v_lshl_add_u64 v[50:51], v[42:43], 0, s[16:17]
	v_lshl_add_u64 v[42:43], v[50:51], 0, v[18:19]
	global_load_dwordx4 v[42:45], v[42:43], off
	s_add_u32 s16, s4, s16
	s_addc_u32 s17, s5, s17
	v_lshl_add_u64 v[54:55], s[16:17], 0, v[18:19]
	v_lshl_add_u64 v[56:57], v[50:51], 0, v[20:21]
	s_waitcnt vmcnt(0)
	ds_write_b128 v2, v[42:45]
	ds_read_b128 v[46:49], v3 offset:33536
	ds_read2st64_b32 v[52:53], v26 offset0:129 offset1:130
	s_waitcnt lgkmcnt(0)
	v_pk_mul_f32 v[48:49], v[48:49], v[52:53] op_sel_hi:[1,0]
	v_pk_mul_f32 v[46:47], v[46:47], v[52:53] op_sel_hi:[1,0]
	v_mov_b32_e32 v52, v53
	v_pk_fma_f32 v[44:45], v[44:45], v[52:53], v[48:49] op_sel_hi:[1,0,1]
	v_pk_fma_f32 v[42:43], v[42:43], v[52:53], v[46:47] op_sel_hi:[1,0,1]
	global_store_dwordx4 v[54:55], v[42:45], off
	global_load_dwordx4 v[42:45], v[56:57], off
	v_lshl_add_u64 v[54:55], s[16:17], 0, v[20:21]
	v_lshl_add_u64 v[56:57], v[50:51], 0, v[22:23]
	v_lshl_add_u64 v[50:51], v[50:51], 0, v[24:25]
	s_waitcnt vmcnt(0)
	ds_write_b128 v7, v[42:45]
	ds_read_b128 v[46:49], v3 offset:33536
	ds_read2st64_b32 v[52:53], v27 offset0:129 offset1:130
	s_waitcnt lgkmcnt(0)
	v_pk_mul_f32 v[48:49], v[48:49], v[52:53] op_sel_hi:[1,0]
	v_pk_mul_f32 v[46:47], v[46:47], v[52:53] op_sel_hi:[1,0]
	v_mov_b32_e32 v52, v53
	v_pk_fma_f32 v[44:45], v[44:45], v[52:53], v[48:49] op_sel_hi:[1,0,1]
	v_pk_fma_f32 v[42:43], v[42:43], v[52:53], v[46:47] op_sel_hi:[1,0,1]
	global_store_dwordx4 v[54:55], v[42:45], off
	global_load_dwordx4 v[42:45], v[56:57], off
	v_lshl_add_u64 v[54:55], s[16:17], 0, v[22:23]
	s_waitcnt vmcnt(0)
	ds_write_b128 v30, v[42:45]
	ds_read_b128 v[46:49], v3 offset:33536
	ds_read2st64_b32 v[52:53], v28 offset0:129 offset1:130
	s_waitcnt lgkmcnt(0)
	v_pk_mul_f32 v[48:49], v[48:49], v[52:53] op_sel_hi:[1,0]
	v_pk_mul_f32 v[46:47], v[46:47], v[52:53] op_sel_hi:[1,0]
	v_mov_b32_e32 v52, v53
	v_pk_fma_f32 v[44:45], v[44:45], v[52:53], v[48:49] op_sel_hi:[1,0,1]
	v_pk_fma_f32 v[42:43], v[42:43], v[52:53], v[46:47] op_sel_hi:[1,0,1]
	global_store_dwordx4 v[54:55], v[42:45], off
	global_load_dwordx4 v[42:45], v[50:51], off
	v_lshl_add_u64 v[52:53], s[16:17], 0, v[24:25]
	s_waitcnt vmcnt(0)
	ds_write_b128 v31, v[42:45]
	ds_read_b128 v[46:49], v3 offset:33536
	ds_read2st64_b32 v[50:51], v29 offset0:129 offset1:130
	s_waitcnt lgkmcnt(0)
	v_pk_mul_f32 v[48:49], v[48:49], v[50:51] op_sel_hi:[1,0]
	v_pk_mul_f32 v[46:47], v[46:47], v[50:51] op_sel_hi:[1,0]
	v_mov_b32_e32 v50, v51
	v_pk_fma_f32 v[44:45], v[44:45], v[50:51], v[48:49] op_sel_hi:[1,0,1]
	v_pk_fma_f32 v[42:43], v[42:43], v[50:51], v[46:47] op_sel_hi:[1,0,1]
	global_store_dwordx4 v[52:53], v[42:45], off
	s_waitcnt lgkmcnt(0)
	s_barrier
	v_mov_b32_e32 v42, 0
	s_and_saveexec_b64 s[16:17], s[8:9]
	s_cbranch_execz .LBB0_4261
	v_mov_b32_e32 v42, 0
	s_mov_b32 s21, 0
	s_mov_b32 s24, s27

.LBB0_4261:
	s_or_b64 exec, exec, s[16:17]
	s_waitcnt lgkmcnt(0)
	s_barrier
	s_and_saveexec_b64 s[24:25], s[8:9]
	s_cbranch_execz .LBB0_4246
	v_mov_b32_e32 v43, s37
	v_mov_b64_e32 v[46:47], s[0:1]
	ds_read2_b32 v[44:45], v43 offset1:1
	global_load_dwordx2 v[46:47], v[46:47], off offset:168 sc0 sc1
	s_waitcnt vmcnt(0)
	v_lshl_add_u64 v[48:49], v[12:13], 2, s[22:23]
	global_load_dword v43, v[48:49], off
	s_waitcnt lgkmcnt(0)
	v_add_f32_e32 v44, v44, v45
	v_fmamk_f32 v44, v44, 0x3c000000, v32
	v_mul_f32_e32 v45, 0x4f800000, v44
	v_cmp_gt_f32_e32 vcc, s41, v44
	v_lshl_add_u64 v[46:47], v[130:131], 2, v[46:47]
	global_load_dword v46, v[46:47], off offset:512
	v_cndmask_b32_e32 v44, v44, v45, vcc
	v_sqrt_f32_e32 v45, v44
	s_nop 0
	v_add_u32_e32 v47, -1, v45
	v_add_u32_e32 v48, 1, v45
	v_fma_f32 v49, -v47, v45, v44
	v_fma_f32 v50, -v48, v45, v44
	v_cmp_ge_f32_e64 s[16:17], 0, v49
	s_nop 1
	v_cndmask_b32_e64 v45, v45, v47, s[16:17]
	v_cmp_lt_f32_e64 s[16:17], 0, v50
	s_nop 1
	v_cndmask_b32_e64 v45, v45, v48, s[16:17]
	v_mul_f32_e32 v47, 0x37800000, v45
	v_cndmask_b32_e32 v45, v45, v47, vcc
	v_cmp_class_f32_e32 vcc, v44, v33
	s_nop 1
	v_cndmask_b32_e32 v44, v45, v44, vcc
	v_div_scale_f32 v45, s[16:17], v44, v44, 1.0
	v_rcp_f32_e32 v47, v45
	v_div_scale_f32 v48, vcc, 1.0, v44, 1.0
	s_lshl_b64 s[16:17], s[18:19], 11
	v_fma_f32 v49, -v45, v47, 1.0
	v_fmac_f32_e32 v47, v49, v47
	v_mul_f32_e32 v49, v48, v47
	v_fma_f32 v50, -v45, v49, v48
	v_fmac_f32_e32 v49, v50, v47
	v_fma_f32 v45, -v45, v49, v48
	s_waitcnt vmcnt(0)
	v_mul_f32_e32 v48, 0xbfb8aa3b, v43
	v_exp_f32_e32 v48, v48
	v_div_fmas_f32 v45, v45, v47, v49
	v_div_fixup_f32 v44, v45, v44, 1.0
	v_mul_f32_e32 v42, v42, v44
	v_add_f32_e32 v45, 1.0, v48
	v_div_scale_f32 v47, s[22:23], v45, v45, v43
	v_rcp_f32_e32 v48, v47
	v_div_scale_f32 v44, vcc, v43, v45, v43
	v_fma_f32 v49, -v47, v48, 1.0
	v_fmac_f32_e32 v48, v49, v48
	v_mul_f32_e32 v49, v44, v48
	v_fma_f32 v50, -v47, v49, v44
	v_fmac_f32_e32 v49, v50, v48
	v_fma_f32 v44, -v47, v49, v44
	v_div_fmas_f32 v44, v44, v48, v49
	v_div_fixup_f32 v43, v44, v45, v43
	v_mul_f32_e32 v42, v46, v42
	v_mul_f32_e32 v42, v42, v43
	v_bfe_u32 v43, v42, 16, 1
	v_add3_u32 v44, v42, v43, s42
	v_lshl_add_u64 v[42:43], v[14:15], 0, s[16:17]
	global_store_short_d16_hi v[42:43], v44, off
	s_branch .LBB0_4246

.LBB0_4318:
	s_cmp_lt_i32 s90, 22
	s_cselect_b64 s[2:3], -1, 0
	s_cmp_gt_i32 s91, 21
	s_cselect_b64 s[4:5], -1, 0
	s_and_b64 s[2:3], s[2:3], s[4:5]
	s_andn2_b64 vcc, exec, s[2:3]
	s_cbranch_vccnz .LBB0_4865
	s_add_u32 s2, s38, 0x31600000
	s_addc_u32 s3, s39, 0
	s_cmp_gt_i32 s40, 15
	s_cselect_b64 s[4:5], -1, 0
	s_and_b32 s6, s40, 6
	s_cmp_eq_u32 s6, 6
	s_cselect_b64 s[6:7], -1, 0
	s_ashr_i32 s41, s40, 31
	s_or_b64 s[14:15], s[4:5], s[6:7]
	s_lshl_b32 s8, s96, 5
	s_lshl_b64 s[4:5], s[40:41], 18
	s_add_u32 s4, s2, s4
	s_addc_u32 s5, s3, s5
	s_add_u32 s16, s4, 0x80000
	s_addc_u32 s17, s5, 0
	s_ashr_i32 s9, s8, 31
	s_lshl_b64 s[6:7], s[8:9], 10
	s_add_u32 s6, s4, s6
	s_addc_u32 s7, s5, s7
	s_add_u32 s9, s6, 0x800
	s_addc_u32 s12, s7, 0
	v_mov_b32_e32 v133, 0
	s_and_b64 s[10:11], s[14:15], exec
	s_cselect_b32 s10, s6, s16
	s_cselect_b32 s11, s7, s17
	s_cmp_lt_i32 s96, 8
	v_lshlrev_b64 v[24:25], 2, v[132:133]
	s_cselect_b32 s11, s12, s11
	s_cselect_b32 s10, s9, s10
	v_lshl_add_u64 v[2:3], s[6:7], 0, v[24:25]
	s_or_b32 s6, s8, 1
	s_ashr_i32 s7, s6, 31
	global_load_dword v20, v[2:3], off
	global_load_dword v21, v[2:3], off offset:256
	v_lshl_add_u64 v[2:3], s[10:11], 0, v[24:25]
	s_lshl_b64 s[10:11], s[6:7], 10
	s_add_u32 s10, s4, s10
	s_addc_u32 s11, s5, s11
	s_add_u32 s18, s10, 0x800
	s_addc_u32 s7, s11, 0
	s_add_u32 s9, s4, 0x80400
	s_addc_u32 s26, s5, 0
	s_and_b64 s[12:13], s[14:15], exec
	s_cselect_b32 s12, s10, s9
	s_cselect_b32 s13, s11, s26
	s_cmpk_lt_i32 s6, 0xfe
	s_cselect_b32 s7, s7, s13
	s_cselect_b32 s6, s18, s12
	s_or_b32 s88, s8, 2
	global_load_dword v22, v[2:3], off offset:512
	global_load_dword v23, v[2:3], off offset:768
	v_lshl_add_u64 v[2:3], s[10:11], 0, v[24:25]
	s_ashr_i32 s89, s88, 31
	global_load_dword v107, v[2:3], off
	global_load_dword v105, v[2:3], off offset:256
	v_lshl_add_u64 v[2:3], s[6:7], 0, v[24:25]
	s_lshl_b64 s[6:7], s[88:89], 10
	s_add_u32 s6, s4, s6
	s_addc_u32 s7, s5, s7
	s_add_u32 s12, s6, 0x800
	s_addc_u32 s13, s7, 0
	s_and_b64 s[10:11], s[14:15], exec
	s_cselect_b32 s10, s6, s16
	s_cselect_b32 s11, s7, s17
	s_cmpk_lt_i32 s88, 0xfe
	s_cselect_b32 s11, s13, s11
	s_cselect_b32 s10, s12, s10
	s_or_b32 s86, s8, 3
	s_ashr_i32 s87, s86, 31
	global_load_dword v108, v[2:3], off offset:512
	global_load_dword v106, v[2:3], off offset:768
	v_lshl_add_u64 v[2:3], s[6:7], 0, v[24:25]
	s_lshl_b64 s[6:7], s[86:87], 10
	s_add_u32 s6, s4, s6
	s_addc_u32 s7, s5, s7
	s_add_u32 s12, s6, 0x800
	s_addc_u32 s13, s7, 0
	global_load_dword v103, v[2:3], off
	global_load_dword v100, v[2:3], off offset:256
	v_lshl_add_u64 v[2:3], s[10:11], 0, v[24:25]
	s_and_b64 s[10:11], s[14:15], exec
	s_cselect_b32 s10, s6, s9
	s_cselect_b32 s11, s7, s26
	s_cmpk_lt_i32 s86, 0xfe
	s_cselect_b32 s11, s13, s11
	s_cselect_b32 s10, s12, s10
	s_or_b32 s84, s8, 4
	s_ashr_i32 s85, s84, 31
	global_load_dword v104, v[2:3], off offset:512
	global_load_dword v102, v[2:3], off offset:768
	v_lshl_add_u64 v[2:3], s[6:7], 0, v[24:25]
	s_lshl_b64 s[6:7], s[84:85], 10
	s_add_u32 s6, s4, s6
	s_addc_u32 s7, s5, s7
	s_add_u32 s12, s6, 0x800
	s_addc_u32 s13, s7, 0
	global_load_dword v98, v[2:3], off
	global_load_dword v97, v[2:3], off offset:256
	v_lshl_add_u64 v[2:3], s[10:11], 0, v[24:25]
	s_and_b64 s[10:11], s[14:15], exec
	s_cselect_b32 s10, s6, s16
	s_cselect_b32 s11, s7, s17
	s_cmpk_lt_i32 s84, 0xfe
	s_cselect_b32 s11, s13, s11
	s_cselect_b32 s10, s12, s10
	s_or_b32 s82, s8, 5
	s_ashr_i32 s83, s82, 31
	global_load_dword v101, v[2:3], off offset:512
	global_load_dword v99, v[2:3], off offset:768
	v_lshl_add_u64 v[2:3], s[6:7], 0, v[24:25]
	s_lshl_b64 s[6:7], s[82:83], 10
	s_add_u32 s6, s4, s6
	s_addc_u32 s7, s5, s7
	s_add_u32 s12, s6, 0x800
	s_addc_u32 s13, s7, 0
	global_load_dword v94, v[2:3], off
	global_load_dword v93, v[2:3], off offset:256
	v_lshl_add_u64 v[2:3], s[10:11], 0, v[24:25]
	s_and_b64 s[10:11], s[14:15], exec
	s_cselect_b32 s10, s6, s9
	s_cselect_b32 s11, s7, s26
	s_cmpk_lt_i32 s82, 0xfe
	s_cselect_b32 s11, s13, s11
	s_cselect_b32 s10, s12, s10
	s_or_b32 s80, s8, 6
	s_ashr_i32 s81, s80, 31
	global_load_dword v96, v[2:3], off offset:512
	global_load_dword v95, v[2:3], off offset:768
	v_lshl_add_u64 v[2:3], s[6:7], 0, v[24:25]
	s_lshl_b64 s[6:7], s[80:81], 10
	s_add_u32 s6, s4, s6
	s_addc_u32 s7, s5, s7
	s_add_u32 s12, s6, 0x800
	s_addc_u32 s13, s7, 0
	global_load_dword v90, v[2:3], off
	global_load_dword v89, v[2:3], off offset:256
	v_lshl_add_u64 v[2:3], s[10:11], 0, v[24:25]
	s_and_b64 s[10:11], s[14:15], exec
	s_cselect_b32 s10, s6, s16
	s_cselect_b32 s11, s7, s17
	s_cmpk_lt_i32 s80, 0xfe
	s_cselect_b32 s11, s13, s11
	s_cselect_b32 s10, s12, s10
	s_or_b32 s78, s8, 7
	s_ashr_i32 s79, s78, 31
	global_load_dword v92, v[2:3], off offset:512
	global_load_dword v91, v[2:3], off offset:768
	v_lshl_add_u64 v[2:3], s[6:7], 0, v[24:25]
	s_lshl_b64 s[6:7], s[78:79], 10
	s_add_u32 s6, s4, s6
	s_addc_u32 s7, s5, s7
	s_add_u32 s12, s6, 0x800
	s_addc_u32 s13, s7, 0
	global_load_dword v87, v[2:3], off
	global_load_dword v85, v[2:3], off offset:256
	v_lshl_add_u64 v[2:3], s[10:11], 0, v[24:25]
	s_and_b64 s[10:11], s[14:15], exec
	s_cselect_b32 s10, s6, s9
	s_cselect_b32 s11, s7, s26
	s_cmpk_lt_i32 s78, 0xfe
	s_cselect_b32 s11, s13, s11
	s_cselect_b32 s10, s12, s10
	s_or_b32 s76, s8, 8
	s_ashr_i32 s77, s76, 31
	global_load_dword v88, v[2:3], off offset:512
	global_load_dword v86, v[2:3], off offset:768
	v_lshl_add_u64 v[2:3], s[6:7], 0, v[24:25]
	s_lshl_b64 s[6:7], s[76:77], 10
	s_add_u32 s6, s4, s6
	s_addc_u32 s7, s5, s7
	s_add_u32 s12, s6, 0x800
	s_addc_u32 s13, s7, 0
	global_load_dword v82, v[2:3], off
	global_load_dword v81, v[2:3], off offset:256
	v_lshl_add_u64 v[2:3], s[10:11], 0, v[24:25]
	s_and_b64 s[10:11], s[14:15], exec
	s_cselect_b32 s10, s6, s16
	s_cselect_b32 s11, s7, s17
	s_cmpk_lt_i32 s76, 0xfe
	s_cselect_b32 s11, s13, s11
	s_cselect_b32 s10, s12, s10
	s_or_b32 s74, s8, 9
	s_ashr_i32 s75, s74, 31
	global_load_dword v84, v[2:3], off offset:512
	global_load_dword v83, v[2:3], off offset:768
	v_lshl_add_u64 v[2:3], s[6:7], 0, v[24:25]
	s_lshl_b64 s[6:7], s[74:75], 10
	s_add_u32 s6, s4, s6
	s_addc_u32 s7, s5, s7
	s_add_u32 s12, s6, 0x800
	s_addc_u32 s13, s7, 0
	global_load_dword v79, v[2:3], off
	global_load_dword v77, v[2:3], off offset:256
	v_lshl_add_u64 v[2:3], s[10:11], 0, v[24:25]
	s_and_b64 s[10:11], s[14:15], exec
	s_cselect_b32 s10, s6, s9
	s_cselect_b32 s11, s7, s26
	s_cmpk_lt_i32 s74, 0xfe
	s_cselect_b32 s11, s13, s11
	s_cselect_b32 s10, s12, s10
	s_or_b32 s70, s8, 10
	s_ashr_i32 s71, s70, 31
	global_load_dword v80, v[2:3], off offset:512
	global_load_dword v78, v[2:3], off offset:768
	v_lshl_add_u64 v[2:3], s[6:7], 0, v[24:25]
	s_lshl_b64 s[6:7], s[70:71], 10
	s_add_u32 s6, s4, s6
	s_addc_u32 s7, s5, s7
	s_add_u32 s12, s6, 0x800
	s_addc_u32 s13, s7, 0
	global_load_dword v73, v[2:3], off
	global_load_dword v72, v[2:3], off offset:256
	v_lshl_add_u64 v[2:3], s[10:11], 0, v[24:25]
	s_and_b64 s[10:11], s[14:15], exec
	s_cselect_b32 s10, s6, s16
	s_cselect_b32 s11, s7, s17
	s_cmpk_lt_i32 s70, 0xfe
	s_cselect_b32 s11, s13, s11
	s_cselect_b32 s10, s12, s10
	s_or_b32 s68, s8, 11
	s_ashr_i32 s69, s68, 31
	global_load_dword v75, v[2:3], off offset:512
	global_load_dword v74, v[2:3], off offset:768
	v_lshl_add_u64 v[2:3], s[6:7], 0, v[24:25]
	s_lshl_b64 s[6:7], s[68:69], 10
	s_add_u32 s6, s4, s6
	s_addc_u32 s7, s5, s7
	s_add_u32 s12, s6, 0x800
	s_addc_u32 s13, s7, 0
	global_load_dword v70, v[2:3], off
	global_load_dword v68, v[2:3], off offset:256
	v_lshl_add_u64 v[2:3], s[10:11], 0, v[24:25]
	s_and_b64 s[10:11], s[14:15], exec
	s_cselect_b32 s10, s6, s9
	s_cselect_b32 s11, s7, s26
	s_cmpk_lt_i32 s68, 0xfe
	s_cselect_b32 s11, s13, s11
	s_cselect_b32 s10, s12, s10
	s_or_b32 s66, s8, 12
	s_ashr_i32 s67, s66, 31
	global_load_dword v71, v[2:3], off offset:512
	global_load_dword v69, v[2:3], off offset:768
	v_lshl_add_u64 v[2:3], s[6:7], 0, v[24:25]
	s_lshl_b64 s[6:7], s[66:67], 10
	s_add_u32 s6, s4, s6
	s_addc_u32 s7, s5, s7
	s_add_u32 s12, s6, 0x800
	s_addc_u32 s13, s7, 0
	global_load_dword v65, v[2:3], off
	global_load_dword v64, v[2:3], off offset:256
	v_lshl_add_u64 v[2:3], s[10:11], 0, v[24:25]
	s_and_b64 s[10:11], s[14:15], exec
	s_cselect_b32 s10, s6, s16
	s_cselect_b32 s11, s7, s17
	s_cmpk_lt_i32 s66, 0xfe
	s_cselect_b32 s11, s13, s11
	s_cselect_b32 s10, s12, s10
	s_or_b32 s64, s8, 13
	s_ashr_i32 s65, s64, 31
	global_load_dword v67, v[2:3], off offset:512
	global_load_dword v66, v[2:3], off offset:768
	v_lshl_add_u64 v[2:3], s[6:7], 0, v[24:25]
	s_lshl_b64 s[6:7], s[64:65], 10
	s_add_u32 s6, s4, s6
	s_addc_u32 s7, s5, s7
	s_add_u32 s12, s6, 0x800
	s_addc_u32 s13, s7, 0
	global_load_dword v62, v[2:3], off
	global_load_dword v60, v[2:3], off offset:256
	v_lshl_add_u64 v[2:3], s[10:11], 0, v[24:25]
	s_and_b64 s[10:11], s[14:15], exec
	s_cselect_b32 s10, s6, s9
	s_cselect_b32 s11, s7, s26
	s_cmpk_lt_i32 s64, 0xfe
	global_load_dword v63, v[2:3], off offset:512
	global_load_dword v61, v[2:3], off offset:768
	s_cselect_b32 s11, s13, s11
	s_cselect_b32 s10, s12, s10
	v_lshl_add_u64 v[2:3], s[6:7], 0, v[24:25]
	global_load_dword v56, v[2:3], off
	global_load_dword v55, v[2:3], off offset:256
	v_lshl_add_u64 v[2:3], s[10:11], 0, v[24:25]
	s_or_b32 s10, s8, 14
	s_ashr_i32 s11, s10, 31
	s_lshl_b64 s[6:7], s[10:11], 10
	s_add_u32 s6, s4, s6
	s_addc_u32 s7, s5, s7
	s_add_u32 s11, s6, 0x800
	s_addc_u32 s18, s7, 0
	s_and_b64 s[12:13], s[14:15], exec
	s_cselect_b32 s12, s6, s16
	s_cselect_b32 s13, s7, s17
	s_cmpk_lt_i32 s10, 0xfe
	global_load_dword v58, v[2:3], off offset:512
	global_load_dword v57, v[2:3], off offset:768
	s_cselect_b32 s13, s18, s13
	s_cselect_b32 s12, s11, s12
	v_lshl_add_u64 v[2:3], s[6:7], 0, v[24:25]
	s_or_b32 s6, s8, 15
	s_ashr_i32 s7, s6, 31
	global_load_dword v53, v[2:3], off
	global_load_dword v51, v[2:3], off offset:256
	v_lshl_add_u64 v[2:3], s[12:13], 0, v[24:25]
	s_lshl_b64 s[12:13], s[6:7], 10
	s_add_u32 s12, s4, s12
	s_addc_u32 s13, s5, s13
	s_add_u32 s7, s12, 0x800
	s_addc_u32 s11, s13, 0
	s_and_b64 s[18:19], s[14:15], exec
	s_cselect_b32 s18, s12, s9
	s_cselect_b32 s19, s13, s26
	s_cmpk_lt_i32 s6, 0xfe
	global_load_dword v54, v[2:3], off offset:512
	global_load_dword v52, v[2:3], off offset:768
	s_cselect_b32 s19, s11, s19
	s_cselect_b32 s18, s7, s18
	v_lshl_add_u64 v[2:3], s[12:13], 0, v[24:25]
	s_or_b32 s12, s8, 16
	s_ashr_i32 s13, s12, 31
	global_load_dword v49, v[2:3], off
	global_load_dword v1, v[2:3], off offset:256
	v_lshl_add_u64 v[2:3], s[18:19], 0, v[24:25]
	s_lshl_b64 s[18:19], s[12:13], 10
	s_add_u32 s18, s4, s18
	s_addc_u32 s19, s5, s19
	s_add_u32 s7, s18, 0x800
	s_addc_u32 s11, s19, 0
	s_and_b64 s[20:21], s[14:15], exec
	s_cselect_b32 s13, s18, s16
	s_cselect_b32 s20, s19, s17
	s_cmpk_lt_i32 s12, 0xfe
	s_cselect_b32 s21, s11, s20
	s_cselect_b32 s20, s7, s13
	s_or_b32 s62, s8, 17
	s_ashr_i32 s63, s62, 31
	global_load_dword v50, v[2:3], off offset:512
	global_load_dword v48, v[2:3], off offset:768
	v_lshl_add_u64 v[2:3], s[18:19], 0, v[24:25]
	s_lshl_b64 s[18:19], s[62:63], 10
	s_add_u32 s18, s4, s18
	s_addc_u32 s19, s5, s19
	s_add_u32 s7, s18, 0x800
	s_addc_u32 s11, s19, 0
	global_load_dword v38, v[2:3], off
	global_load_dword v39, v[2:3], off offset:256
	v_lshl_add_u64 v[2:3], s[20:21], 0, v[24:25]
	s_and_b64 s[20:21], s[14:15], exec
	s_cselect_b32 s13, s18, s9
	s_cselect_b32 s20, s19, s26
	s_cmpk_lt_i32 s62, 0xfe
	s_cselect_b32 s21, s11, s20
	s_cselect_b32 s20, s7, s13
	s_or_b32 s60, s8, 18
	s_ashr_i32 s61, s60, 31
	global_load_dword v36, v[2:3], off offset:512
	global_load_dword v37, v[2:3], off offset:768
	v_lshl_add_u64 v[2:3], s[18:19], 0, v[24:25]
	s_lshl_b64 s[18:19], s[60:61], 10
	s_add_u32 s18, s4, s18
	s_addc_u32 s19, s5, s19
	s_add_u32 s7, s18, 0x800
	s_addc_u32 s11, s19, 0
	global_load_dword v177, v[2:3], off
	global_load_dword v175, v[2:3], off offset:256
	v_lshl_add_u64 v[2:3], s[20:21], 0, v[24:25]
	s_and_b64 s[20:21], s[14:15], exec
	s_cselect_b32 s13, s18, s16
	s_cselect_b32 s20, s19, s17
	s_cmpk_lt_i32 s60, 0xfe
	s_cselect_b32 s21, s11, s20
	s_cselect_b32 s20, s7, s13
	s_or_b32 s58, s8, 19
	s_ashr_i32 s59, s58, 31
	global_load_dword v178, v[2:3], off offset:512
	global_load_dword v176, v[2:3], off offset:768
	v_lshl_add_u64 v[2:3], s[18:19], 0, v[24:25]
	s_lshl_b64 s[18:19], s[58:59], 10
	s_add_u32 s18, s4, s18
	s_addc_u32 s19, s5, s19
	s_add_u32 s7, s18, 0x800
	s_addc_u32 s11, s19, 0
	global_load_dword v173, v[2:3], off
	global_load_dword v171, v[2:3], off offset:256
	v_lshl_add_u64 v[2:3], s[20:21], 0, v[24:25]
	s_and_b64 s[20:21], s[14:15], exec
	s_cselect_b32 s13, s18, s9
	s_cselect_b32 s20, s19, s26
	s_cmpk_lt_i32 s58, 0xfe
	s_cselect_b32 s21, s11, s20
	s_cselect_b32 s20, s7, s13
	s_or_b32 s56, s8, 20
	s_ashr_i32 s57, s56, 31
	global_load_dword v174, v[2:3], off offset:512
	global_load_dword v172, v[2:3], off offset:768
	v_lshl_add_u64 v[2:3], s[18:19], 0, v[24:25]
	s_lshl_b64 s[18:19], s[56:57], 10
	s_add_u32 s18, s4, s18
	s_addc_u32 s19, s5, s19
	s_add_u32 s7, s18, 0x800
	s_addc_u32 s11, s19, 0
	global_load_dword v169, v[2:3], off
	global_load_dword v167, v[2:3], off offset:256
	v_lshl_add_u64 v[2:3], s[20:21], 0, v[24:25]
	s_and_b64 s[20:21], s[14:15], exec
	s_cselect_b32 s13, s18, s16
	s_cselect_b32 s20, s19, s17
	s_cmpk_lt_i32 s56, 0xfe
	s_cselect_b32 s21, s11, s20
	s_cselect_b32 s20, s7, s13
	s_or_b32 s54, s8, 21
	s_ashr_i32 s55, s54, 31
	global_load_dword v170, v[2:3], off offset:512
	global_load_dword v168, v[2:3], off offset:768
	v_lshl_add_u64 v[2:3], s[18:19], 0, v[24:25]
	s_lshl_b64 s[18:19], s[54:55], 10
	s_add_u32 s18, s4, s18
	s_addc_u32 s19, s5, s19
	s_add_u32 s7, s18, 0x800
	s_addc_u32 s11, s19, 0
	global_load_dword v165, v[2:3], off
	global_load_dword v163, v[2:3], off offset:256
	v_lshl_add_u64 v[2:3], s[20:21], 0, v[24:25]
	s_and_b64 s[20:21], s[14:15], exec
	s_cselect_b32 s13, s18, s9
	s_cselect_b32 s20, s19, s26
	s_cmpk_lt_i32 s54, 0xfe
	s_cselect_b32 s21, s11, s20
	s_cselect_b32 s20, s7, s13
	s_or_b32 s52, s8, 22
	s_ashr_i32 s53, s52, 31
	global_load_dword v166, v[2:3], off offset:512
	global_load_dword v164, v[2:3], off offset:768
	v_lshl_add_u64 v[2:3], s[18:19], 0, v[24:25]
	s_lshl_b64 s[18:19], s[52:53], 10
	s_add_u32 s18, s4, s18
	s_addc_u32 s19, s5, s19
	s_add_u32 s7, s18, 0x800
	s_addc_u32 s11, s19, 0
	global_load_dword v161, v[2:3], off
	global_load_dword v159, v[2:3], off offset:256
	v_lshl_add_u64 v[2:3], s[20:21], 0, v[24:25]
	s_and_b64 s[20:21], s[14:15], exec
	s_cselect_b32 s13, s18, s16
	s_cselect_b32 s20, s19, s17
	s_cmpk_lt_i32 s52, 0xfe
	s_cselect_b32 s21, s11, s20
	s_cselect_b32 s20, s7, s13
	s_or_b32 s50, s8, 23
	s_ashr_i32 s51, s50, 31
	global_load_dword v162, v[2:3], off offset:512
	global_load_dword v160, v[2:3], off offset:768
	v_lshl_add_u64 v[2:3], s[18:19], 0, v[24:25]
	s_lshl_b64 s[18:19], s[50:51], 10
	s_add_u32 s18, s4, s18
	s_addc_u32 s19, s5, s19
	s_add_u32 s7, s18, 0x800
	s_addc_u32 s11, s19, 0
	global_load_dword v157, v[2:3], off
	global_load_dword v155, v[2:3], off offset:256
	v_lshl_add_u64 v[2:3], s[20:21], 0, v[24:25]
	s_and_b64 s[20:21], s[14:15], exec
	s_cselect_b32 s13, s18, s9
	s_cselect_b32 s20, s19, s26
	s_cmpk_lt_i32 s50, 0xfe
	s_cselect_b32 s21, s11, s20
	s_cselect_b32 s20, s7, s13
	s_or_b32 s48, s8, 24
	s_ashr_i32 s49, s48, 31
	global_load_dword v158, v[2:3], off offset:512
	global_load_dword v156, v[2:3], off offset:768
	v_lshl_add_u64 v[2:3], s[18:19], 0, v[24:25]
	s_lshl_b64 s[18:19], s[48:49], 10
	s_add_u32 s18, s4, s18
	s_addc_u32 s19, s5, s19
	s_add_u32 s7, s18, 0x800
	s_addc_u32 s11, s19, 0
	global_load_dword v153, v[2:3], off
	global_load_dword v151, v[2:3], off offset:256
	v_lshl_add_u64 v[2:3], s[20:21], 0, v[24:25]
	s_and_b64 s[20:21], s[14:15], exec
	s_cselect_b32 s13, s18, s16
	s_cselect_b32 s20, s19, s17
	s_cmpk_lt_i32 s48, 0xfe
	s_cselect_b32 s21, s11, s20
	s_cselect_b32 s20, s7, s13
	s_or_b32 s46, s8, 25
	s_ashr_i32 s47, s46, 31
	global_load_dword v154, v[2:3], off offset:512
	global_load_dword v152, v[2:3], off offset:768
	v_lshl_add_u64 v[2:3], s[18:19], 0, v[24:25]
	s_lshl_b64 s[18:19], s[46:47], 10
	s_add_u32 s18, s4, s18
	s_addc_u32 s19, s5, s19
	s_add_u32 s7, s18, 0x800
	s_addc_u32 s11, s19, 0
	global_load_dword v149, v[2:3], off
	global_load_dword v147, v[2:3], off offset:256
	v_lshl_add_u64 v[2:3], s[20:21], 0, v[24:25]
	s_and_b64 s[20:21], s[14:15], exec
	s_cselect_b32 s13, s18, s9
	s_cselect_b32 s20, s19, s26
	s_cmpk_lt_i32 s46, 0xfe
	s_cselect_b32 s21, s11, s20
	s_cselect_b32 s20, s7, s13
	s_or_b32 s44, s8, 26
	s_ashr_i32 s45, s44, 31
	global_load_dword v150, v[2:3], off offset:512
	global_load_dword v148, v[2:3], off offset:768
	v_lshl_add_u64 v[2:3], s[18:19], 0, v[24:25]
	s_lshl_b64 s[18:19], s[44:45], 10
	s_add_u32 s18, s4, s18
	s_addc_u32 s19, s5, s19
	s_add_u32 s7, s18, 0x800
	s_addc_u32 s11, s19, 0
	global_load_dword v145, v[2:3], off
	global_load_dword v143, v[2:3], off offset:256
	v_lshl_add_u64 v[2:3], s[20:21], 0, v[24:25]
	s_and_b64 s[20:21], s[14:15], exec
	s_cselect_b32 s13, s18, s16
	s_cselect_b32 s20, s19, s17
	s_cmpk_lt_i32 s44, 0xfe
	s_cselect_b32 s21, s11, s20
	s_cselect_b32 s20, s7, s13
	s_or_b32 s24, s8, 27
	s_ashr_i32 s25, s24, 31
	global_load_dword v146, v[2:3], off offset:512
	global_load_dword v144, v[2:3], off offset:768
	v_lshl_add_u64 v[2:3], s[18:19], 0, v[24:25]
	s_lshl_b64 s[18:19], s[24:25], 10
	s_add_u32 s18, s4, s18
	s_addc_u32 s19, s5, s19
	s_add_u32 s7, s18, 0x800
	s_addc_u32 s11, s19, 0
	global_load_dword v141, v[2:3], off
	global_load_dword v139, v[2:3], off offset:256
	v_lshl_add_u64 v[2:3], s[20:21], 0, v[24:25]
	s_and_b64 s[20:21], s[14:15], exec
	s_cselect_b32 s13, s18, s9
	s_cselect_b32 s20, s19, s26
	s_cmpk_lt_i32 s24, 0xfe
	s_cselect_b32 s21, s11, s20
	s_cselect_b32 s20, s7, s13
	s_or_b32 s22, s8, 28
	s_ashr_i32 s23, s22, 31
	global_load_dword v142, v[2:3], off offset:512
	global_load_dword v140, v[2:3], off offset:768
	v_lshl_add_u64 v[2:3], s[18:19], 0, v[24:25]
	s_lshl_b64 s[18:19], s[22:23], 10
	s_add_u32 s18, s4, s18
	s_addc_u32 s19, s5, s19
	s_add_u32 s7, s18, 0x800
	s_addc_u32 s11, s19, 0
	global_load_dword v137, v[2:3], off
	global_load_dword v135, v[2:3], off offset:256
	v_lshl_add_u64 v[2:3], s[20:21], 0, v[24:25]
	s_and_b64 s[20:21], s[14:15], exec
	s_cselect_b32 s13, s18, s16
	s_cselect_b32 s20, s19, s17
	s_cmpk_lt_i32 s22, 0xfe
	global_load_dword v138, v[2:3], off offset:512
	global_load_dword v136, v[2:3], off offset:768
	s_cselect_b32 s21, s11, s20
	s_cselect_b32 s20, s7, s13
	v_lshl_add_u64 v[2:3], s[18:19], 0, v[24:25]
	global_load_dword v129, v[2:3], off
	global_load_dword v127, v[2:3], off offset:256
	v_lshl_add_u64 v[2:3], s[20:21], 0, v[24:25]
	s_or_b32 s20, s8, 29
	s_ashr_i32 s21, s20, 31
	s_lshl_b64 s[18:19], s[20:21], 10
	s_add_u32 s18, s4, s18
	s_addc_u32 s19, s5, s19
	s_add_u32 s7, s18, 0x800
	s_addc_u32 s11, s19, 0
	s_and_b64 s[28:29], s[14:15], exec
	s_cselect_b32 s13, s18, s9
	s_cselect_b32 s21, s19, s26
	s_cmpk_lt_i32 s20, 0xfe
	global_load_dword v134, v[2:3], off offset:512
	global_load_dword v128, v[2:3], off offset:768
	s_cselect_b32 s29, s11, s21
	s_cselect_b32 s28, s7, s13
	v_lshl_add_u64 v[2:3], s[18:19], 0, v[24:25]
	s_or_b32 s18, s8, 30
	s_ashr_i32 s19, s18, 31
	global_load_dword v125, v[2:3], off
	global_load_dword v123, v[2:3], off offset:256
	v_lshl_add_u64 v[2:3], s[28:29], 0, v[24:25]
	s_lshl_b64 s[28:29], s[18:19], 10
	s_add_u32 s28, s4, s28
	s_addc_u32 s29, s5, s29
	s_add_u32 s7, s28, 0x800
	s_addc_u32 s11, s29, 0
	s_and_b64 s[30:31], s[14:15], exec
	s_cselect_b32 s13, s28, s16
	s_cselect_b32 s16, s29, s17
	s_cmpk_lt_i32 s18, 0xfe
	global_load_dword v126, v[2:3], off offset:512
	global_load_dword v124, v[2:3], off offset:768
	s_cselect_b32 s17, s11, s16
	s_cselect_b32 s16, s7, s13
	v_lshl_add_u64 v[2:3], s[28:29], 0, v[24:25]
	global_load_dword v121, v[2:3], off
	global_load_dword v119, v[2:3], off offset:256
	v_lshl_add_u64 v[2:3], s[16:17], 0, v[24:25]
	s_or_b32 s16, s8, 31
	s_ashr_i32 s17, s16, 31
	s_lshl_b64 s[28:29], s[16:17], 10
	s_add_u32 s4, s4, s28
	s_addc_u32 s5, s5, s29
	s_add_u32 s7, s4, 0x800
	s_addc_u32 s11, s5, 0
	s_and_b64 s[14:15], s[14:15], exec
	s_cselect_b32 s9, s4, s9
	s_cselect_b32 s13, s5, s26
	s_cmpk_lt_i32 s16, 0xfe
	global_load_dword v122, v[2:3], off offset:512
	global_load_dword v120, v[2:3], off offset:768
	s_cselect_b32 s15, s11, s13
	s_cselect_b32 s14, s7, s9
	v_lshl_add_u64 v[2:3], s[4:5], 0, v[24:25]
	global_load_dword v117, v[2:3], off
	global_load_dword v115, v[2:3], off offset:256
	v_lshl_add_u64 v[2:3], s[14:15], 0, v[24:25]
	global_load_dword v118, v[2:3], off offset:512
	global_load_dword v116, v[2:3], off offset:768
	s_movk_i32 s4, 0x2000
	s_mov_b64 s[14:15], 0x800
	v_cmp_gt_i32_e32 vcc, s4, v130
	v_lshl_add_u32 v4, v130, 2, s94
	s_waitcnt vmcnt(0) lgkmcnt(0)
	s_barrier
	s_and_saveexec_b64 s[72:73], vcc
	s_cbranch_execz .LBB0_4322
	s_and_b32 s4, s40, 1
	s_lshl_b32 s4, s4, 15
	v_mov_b32_e32 v2, s4
	v_mov_b32_e32 v3, v133
	v_ashrrev_i32_e32 v131, 31, v130
	v_lshl_add_u64 v[2:3], v[130:131], 2, v[2:3]
	s_mov_b64 s[4:5], 0x10000
	v_add_u32_e32 v5, 0xfffffe00, v130
	v_lshl_add_u64 v[2:3], v[2:3], 0, s[4:5]
	s_mov_b64 s[90:91], 0
	s_movk_i32 s4, 0x1dff
	v_mov_b32_e32 v6, v4
.LBB0_4321:
	v_mov_b64_e32 v[8:9], s[0:1]
	global_load_dwordx2 v[8:9], v[8:9], off offset:144 sc0 sc1
	s_waitcnt vmcnt(0)
	v_add_u32_e32 v5, 0x200, v5
	v_cmp_lt_i32_e32 vcc, s4, v5
	s_or_b64 s[90:91], vcc, s[90:91]
	s_waitcnt lgkmcnt(0)
	v_lshl_add_u64 v[8:9], v[8:9], 0, v[2:3]
	global_load_dword v7, v[8:9], off
	v_lshl_add_u64 v[2:3], v[2:3], 0, s[14:15]
	s_waitcnt vmcnt(0)
	ds_write_b32 v6, v7
	v_add_u32_e32 v6, 0x800, v6
	s_andn2_b64 exec, exec, s[90:91]
	s_cbranch_execnz .LBB0_4321
.LBB0_4322:
	s_or_b64 exec, exec, s[72:73]
	s_movk_i32 s4, 0x7f
	s_and_b32 s26, s40, 1
	v_cmp_lt_i32_e32 vcc, s4, v130
	s_and_saveexec_b64 s[14:15], vcc
	s_xor_b64 s[14:15], exec, s[14:15]
	s_lshl_b32 s4, s26, 7
	s_or_saveexec_b64 s[14:15], s[14:15]
	v_mov_b32_e32 v59, s4
	s_xor_b64 exec, exec, s[14:15]
	s_cbranch_execz .LBB0_4328
	v_mov_b64_e32 v[2:3], s[0:1]
	global_load_dwordx2 v[6:7], v[2:3], off offset:136 sc0 sc1
	s_waitcnt vmcnt(0)
	s_lshl_b32 s4, s26, 7
	v_add_u32_e32 v2, s4, v130
	v_add_u32_e32 v8, 0x100, v2
	v_ashrrev_i32_e32 v9, 31, v8
	s_add_u32 s72, s38, 0x6200000
	s_addc_u32 s73, s39, 0
	s_mov_b32 s5, 0
	s_waitcnt lgkmcnt(0)
	v_lshl_add_u64 v[6:7], v[8:9], 2, v[6:7]
	global_load_dword v3, v[6:7], off
.LBB0_4326:
	v_add_u32_e32 v5, s5, v2
	v_add_u32_e32 v6, 0x100, v5
	v_add_u32_e32 v8, 0x300, v5
	v_add_u32_e32 v10, 0x500, v5
	v_add_u32_e32 v12, 0x700, v5
	v_add_u32_e32 v14, 0x900, v5
	v_add_u32_e32 v16, 0xb00, v5
	v_add_u32_e32 v18, 0xd00, v5
	v_add_u32_e32 v26, 0xf00, v5
	v_ashrrev_i32_e32 v7, 31, v6
	v_ashrrev_i32_e32 v9, 31, v8
	v_ashrrev_i32_e32 v11, 31, v10
	v_ashrrev_i32_e32 v13, 31, v12
	v_ashrrev_i32_e32 v15, 31, v14
	v_ashrrev_i32_e32 v17, 31, v16
	v_ashrrev_i32_e32 v19, 31, v18
	v_ashrrev_i32_e32 v27, 31, v26
	v_lshl_add_u64 v[6:7], v[6:7], 2, s[72:73]
	v_lshl_add_u64 v[8:9], v[8:9], 2, s[72:73]
	v_lshl_add_u64 v[10:11], v[10:11], 2, s[72:73]
	v_lshl_add_u64 v[12:13], v[12:13], 2, s[72:73]
	v_lshl_add_u64 v[14:15], v[14:15], 2, s[72:73]
	v_lshl_add_u64 v[16:17], v[16:17], 2, s[72:73]
	v_lshl_add_u64 v[18:19], v[18:19], 2, s[72:73]
	v_lshl_add_u64 v[26:27], v[26:27], 2, s[72:73]
	global_load_dword v5, v[6:7], off
	s_nop 0
	global_load_dword v6, v[8:9], off
	global_load_dword v7, v[10:11], off
	s_nop 0
	global_load_dword v8, v[12:13], off
	global_load_dword v9, v[14:15], off
	global_load_dword v10, v[16:17], off
	global_load_dword v11, v[18:19], off
	s_nop 0
	global_load_dword v12, v[26:27], off
	s_addk_i32 s5, 0x1000
	s_cmpk_lg_i32 s5, 0x4000
	s_waitcnt vmcnt(0) lgkmcnt(0)
	v_add_f32_e32 v3, v3, v5
	v_add_f32_e32 v3, v3, v6
	v_add_f32_e32 v3, v3, v7
	v_add_f32_e32 v3, v3, v8
	v_add_f32_e32 v3, v3, v9
	v_add_f32_e32 v3, v3, v10
	v_add_f32_e32 v3, v3, v11
	v_add_f32_e32 v3, v3, v12
	s_cbranch_scc1 .LBB0_4326
	v_mov_b32_e32 v59, s4
	ds_write_b32 v4, v3 offset:32768

.LBB0_4391:
	v_add_u32_e32 v32, s4, v114
	ds_read2_b32 v[28:29], v27 offset1:16
	ds_read2_b32 v[30:31], v32 offset1:4
	v_add_u32_e32 v33, 0x800, v27
	s_add_i32 s4, s4, 64
	s_cmpk_lg_i32 s4, 0x200
	s_waitcnt lgkmcnt(0)
	v_mfma_f32_16x16x4_f32 v[14:17], v30, v28, v[14:17]
	v_mfma_f32_16x16x4_f32 v[10:13], v30, v29, v[10:13]
	ds_read2_b32 v[28:29], v27 offset0:32 offset1:48
	s_waitcnt lgkmcnt(0)
	v_mfma_f32_16x16x4_f32 v[6:9], v30, v28, v[6:9]
	v_mfma_f32_16x16x4_f32 v[2:5], v30, v29, v[2:5]
	v_add_u32_e32 v30, 0x400, v27
	ds_read2_b32 v[28:29], v30 offset1:16
	s_waitcnt lgkmcnt(0)
	v_mfma_f32_16x16x4_f32 v[14:17], v31, v28, v[14:17]
	v_mfma_f32_16x16x4_f32 v[10:13], v31, v29, v[10:13]
	ds_read2_b32 v[28:29], v30 offset0:32 offset1:48
	s_waitcnt lgkmcnt(0)
	v_mfma_f32_16x16x4_f32 v[6:9], v31, v28, v[6:9]
	v_mfma_f32_16x16x4_f32 v[2:5], v31, v29, v[2:5]
	ds_read2_b32 v[28:29], v32 offset0:8 offset1:12
	ds_read2_b32 v[30:31], v33 offset1:16
	s_waitcnt lgkmcnt(0)
	v_mfma_f32_16x16x4_f32 v[14:17], v28, v30, v[14:17]
	v_mfma_f32_16x16x4_f32 v[10:13], v28, v31, v[10:13]
	ds_read2_b32 v[30:31], v33 offset0:32 offset1:48
	s_waitcnt lgkmcnt(0)
	v_mfma_f32_16x16x4_f32 v[6:9], v28, v30, v[6:9]
	v_mfma_f32_16x16x4_f32 v[2:5], v28, v31, v[2:5]
	v_add_u32_e32 v28, 0xc00, v27
	ds_read2_b32 v[30:31], v28 offset1:16
	v_add_u32_e32 v27, 0x1000, v27
	s_waitcnt lgkmcnt(0)
	v_mfma_f32_16x16x4_f32 v[14:17], v29, v30, v[14:17]
	v_mfma_f32_16x16x4_f32 v[10:13], v29, v31, v[10:13]
	ds_read2_b32 v[30:31], v28 offset0:32 offset1:48
	s_waitcnt lgkmcnt(0)
	v_mfma_f32_16x16x4_f32 v[6:9], v29, v30, v[6:9]
	v_mfma_f32_16x16x4_f32 v[2:5], v29, v31, v[2:5]
	s_cbranch_scc1 .LBB0_4391
	s_ashr_i32 s6, s40, 3
	s_lshl_b32 s4, s26, 1
	s_lshl_b32 s27, s9, 7
	s_ashr_i32 s7, s6, 31
	v_add_u32_e32 v131, s8, v112
	s_add_u32 s6, s4, s6
	v_add3_u32 v28, s5, -8, v59
	s_movk_i32 s5, 0xfd
	s_addc_u32 s7, 0, s7
	v_cmp_lt_i32_e32 vcc, s5, v131
	s_lshl_b64 s[66:67], s[6:7], 17
	s_and_b64 s[68:69], s[14:15], vcc
	s_add_u32 s5, s38, 0x28800000
	s_addc_u32 s9, s39, 0
	v_ashrrev_i32_e32 v34, 1, v131
	s_add_u32 s64, s5, s66
	v_add_u32_e32 v32, s27, v34
	s_addc_u32 s65, s9, s67
	s_waitcnt lgkmcnt(0)
	v_mov_b32_e32 v29, 0
	v_ashrrev_i32_e32 v33, 31, v32
	s_add_u32 s10, s38, 0x6600000
	v_lshlrev_b64 v[30:31], 16, v[28:29]
	v_lshlrev_b64 v[32:33], 8, v[32:33]
	s_addc_u32 s11, s39, 0
	v_ashrrev_i32_e32 v35, 31, v34
	v_cndmask_b32_e64 v27, 0, 1, s[72:73]
	s_mov_b64 s[74:75], -1
	v_lshl_add_u64 v[42:43], s[64:65], 0, v[32:33]
	v_lshl_add_u64 v[40:41], s[10:11], 0, v[30:31]
	v_lshlrev_b64 v[34:35], 9, v[34:35]
	v_cmp_ne_u32_e64 s[6:7], 1, v27
	s_andn2_b64 vcc, exec, s[72:73]
	v_lshlrev_b32_e32 v28, 1, v111
	s_cbranch_vccnz .LBB0_4400
	v_cndmask_b32_e64 v27, v14, 0, s[68:69]
	v_bfe_u32 v44, v27, 16, 1
	s_movk_i32 s13, 0x7fff
	v_add3_u32 v27, v27, v44, s13
	v_lshl_add_u64 v[44:45], v[42:43], 0, v[28:29]
	global_store_short_d16_hi v[44:45], v27, off
	s_xor_b64 s[70:71], s[68:69], -1
	v_lshl_add_u64 v[44:45], v[40:41], 0, v[34:35]
	s_cbranch_execz .LBB0_4401

.LBB0_4395:
	v_cndmask_b32_e64 v14, v10, 0, s[68:69]
	v_bfe_u32 v27, v14, 16, 1
	s_movk_i32 s13, 0x7fff
	v_mov_b32_e32 v29, 0
	v_add3_u32 v14, v14, v27, s13
	v_lshl_add_u64 v[46:47], v[42:43], 0, v[28:29]
	global_store_short_d16_hi v[46:47], v14, off offset:32
	s_cbranch_execz .LBB0_4405

.LBB0_4397:
	v_cndmask_b32_e64 v10, v6, 0, s[68:69]
	v_bfe_u32 v14, v10, 16, 1
	s_movk_i32 s13, 0x7fff
	v_mov_b32_e32 v29, 0
	v_add3_u32 v10, v10, v14, s13
	v_lshl_add_u64 v[46:47], v[42:43], 0, v[28:29]
	global_store_short_d16_hi v[46:47], v10, off offset:64
	s_cbranch_execz .LBB0_4409

.LBB0_4399:
	v_cndmask_b32_e64 v6, v2, 0, s[68:69]
	v_bfe_u32 v10, v6, 16, 1
	s_movk_i32 s13, 0x7fff
	v_mov_b32_e32 v29, 0
	v_add3_u32 v6, v6, v10, s13
	v_lshl_add_u64 v[42:43], v[42:43], 0, v[28:29]
	global_store_short_d16_hi v[42:43], v6, off offset:96
	s_cbranch_execnz .LBB0_4416
	s_branch .LBB0_4413

.LBB0_4401:
	s_and_saveexec_b64 s[72:73], s[70:71]
	s_cbranch_execz .LBB0_4403
	v_mov_b32_e32 v27, 0
	v_lshl_add_u64 v[46:47], v[44:45], 0, v[26:27]
	global_store_dword v[46:47], v14, off

.LBB0_4405:
	s_and_saveexec_b64 s[72:73], s[70:71]
	s_cbranch_execz .LBB0_4407
	v_mov_b32_e32 v27, 0
	v_lshl_add_u64 v[46:47], v[44:45], 0, v[26:27]
	global_store_dword v[46:47], v10, off offset:64

.LBB0_4409:
	s_and_saveexec_b64 s[72:73], s[70:71]
	s_cbranch_execz .LBB0_4411
	v_mov_b32_e32 v27, 0
	v_lshl_add_u64 v[46:47], v[44:45], 0, v[26:27]
	global_store_dword v[46:47], v6, off offset:128

.LBB0_4413:
	s_and_saveexec_b64 s[68:69], s[70:71]
	s_cbranch_execz .LBB0_4415
	v_mov_b32_e32 v27, 0
	v_lshl_add_u64 v[42:43], v[44:45], 0, v[26:27]
	global_store_dword v[42:43], v2, off offset:192

.LBB0_4416:
	s_movk_i32 s13, 0xfc
	v_cmp_lt_i32_e32 vcc, s13, v131
	s_and_b64 s[68:69], s[14:15], vcc
	s_add_u32 s66, s38, s66
	s_addc_u32 s67, s39, s67
	v_lshl_add_u64 v[32:33], s[66:67], 0, v[32:33]
	s_mov_b64 s[28:29], 0x28800080
	v_lshl_add_u64 v[42:43], s[38:39], 0, v[30:31]
	s_mov_b64 s[72:73], -1
	v_lshl_add_u64 v[44:45], v[32:33], 0, s[28:29]
	v_lshl_add_u64 v[30:31], v[42:43], 0, v[34:35]
	s_and_b64 vcc, exec, s[6:7]
	s_mov_b64 s[74:75], 0x6600100
	s_cbranch_vccnz .LBB0_4418
	v_cndmask_b32_e64 v2, v15, 0, s[68:69]
	v_bfe_u32 v6, v2, 16, 1
	s_movk_i32 s13, 0x7fff
	v_mov_b32_e32 v29, 0
	v_add3_u32 v2, v2, v6, s13
	v_lshl_add_u64 v[32:33], v[44:45], 0, v[28:29]
	s_mov_b64 s[72:73], 0
	global_store_short_d16_hi v[32:33], v2, off
.LBB0_4418:
	s_xor_b64 s[70:71], s[68:69], -1
	s_andn2_b64 vcc, exec, s[72:73]
	v_lshl_add_u64 v[46:47], v[30:31], 0, s[74:75]
	s_cbranch_vccnz .LBB0_4422
	s_and_saveexec_b64 s[72:73], s[70:71]
	s_cbranch_execz .LBB0_4421
	v_mov_b32_e32 v27, 0
	v_lshl_add_u64 v[30:31], v[46:47], 0, v[26:27]
	global_store_dword v[30:31], v15, off

.LBB0_4422:
	v_or_b32_e32 v109, 16, v111
	s_mov_b64 s[72:73], -1
	s_and_b64 vcc, exec, s[6:7]
	v_lshlrev_b32_e32 v30, 1, v109
	s_cbranch_vccnz .LBB0_4424
	v_cndmask_b32_e64 v2, v11, 0, s[68:69]
	v_bfe_u32 v6, v2, 16, 1
	s_movk_i32 s13, 0x7fff
	v_mov_b32_e32 v31, 0
	v_add3_u32 v2, v2, v6, s13
	v_lshl_add_u64 v[14:15], v[44:45], 0, v[30:31]
	s_mov_b64 s[72:73], 0
	global_store_short_d16_hi v[14:15], v2, off
.LBB0_4424:
	s_andn2_b64 vcc, exec, s[72:73]
	s_cbranch_vccnz .LBB0_4428
	s_and_saveexec_b64 s[72:73], s[70:71]
	s_cbranch_execz .LBB0_4427
	v_lshlrev_b32_e32 v14, 2, v109
	v_mov_b32_e32 v15, 0
	v_lshl_add_u64 v[14:15], v[46:47], 0, v[14:15]
	global_store_dword v[14:15], v11, off

.LBB0_4428:
	v_or_b32_e32 v110, 32, v111
	s_mov_b64 s[72:73], -1
	s_and_b64 vcc, exec, s[6:7]
	v_lshlrev_b32_e32 v32, 1, v110
	s_cbranch_vccnz .LBB0_4430
	v_cndmask_b32_e64 v2, v7, 0, s[68:69]
	v_bfe_u32 v6, v2, 16, 1
	s_movk_i32 s13, 0x7fff
	v_mov_b32_e32 v33, 0
	v_add3_u32 v2, v2, v6, s13
	v_lshl_add_u64 v[10:11], v[44:45], 0, v[32:33]
	s_mov_b64 s[72:73], 0
	global_store_short_d16_hi v[10:11], v2, off
.LBB0_4430:
	s_andn2_b64 vcc, exec, s[72:73]
	s_cbranch_vccnz .LBB0_4434
	s_and_saveexec_b64 s[72:73], s[70:71]
	s_cbranch_execz .LBB0_4433
	v_lshlrev_b32_e32 v10, 2, v110
	v_mov_b32_e32 v11, 0
	v_lshl_add_u64 v[10:11], v[46:47], 0, v[10:11]
	global_store_dword v[10:11], v7, off

.LBB0_4434:
	v_or_b32_e32 v111, 48, v111
	s_mov_b64 s[72:73], -1
	s_and_b64 vcc, exec, s[6:7]
	v_lshlrev_b32_e32 v34, 1, v111
	s_cbranch_vccnz .LBB0_4436
	v_cndmask_b32_e64 v2, v3, 0, s[68:69]
	v_bfe_u32 v6, v2, 16, 1
	s_movk_i32 s13, 0x7fff
	v_mov_b32_e32 v35, 0
	v_add3_u32 v2, v2, v6, s13
	v_lshl_add_u64 v[6:7], v[44:45], 0, v[34:35]
	s_mov_b64 s[72:73], 0
	global_store_short_d16_hi v[6:7], v2, off
.LBB0_4436:
	s_andn2_b64 vcc, exec, s[72:73]
	s_cbranch_vccnz .LBB0_4440
	s_and_saveexec_b64 s[68:69], s[70:71]
	s_cbranch_execz .LBB0_4439
	v_lshlrev_b32_e32 v6, 2, v111
	v_mov_b32_e32 v7, 0
	v_lshl_add_u64 v[6:7], v[46:47], 0, v[6:7]
	global_store_dword v[6:7], v3, off

.LBB0_4440:
	v_or_b32_e32 v2, 2, v131
	v_ashrrev_i32_e32 v6, 1, v2
	s_movk_i32 s13, 0xfd
	v_cmp_lt_i32_e32 vcc, s13, v2
	v_add_u32_e32 v2, s27, v6
	v_ashrrev_i32_e32 v3, 31, v2
	v_lshlrev_b64 v[2:3], 8, v[2:3]
	v_ashrrev_i32_e32 v7, 31, v6
	s_and_b64 s[68:69], s[14:15], vcc
	s_mov_b64 s[72:73], -1
	v_lshl_add_u64 v[2:3], s[64:65], 0, v[2:3]
	s_and_b64 vcc, exec, s[6:7]
	v_lshlrev_b64 v[6:7], 9, v[6:7]
	s_cbranch_vccnz .LBB0_4448
	v_cndmask_b32_e64 v10, v16, 0, s[68:69]
	v_bfe_u32 v11, v10, 16, 1
	s_movk_i32 s13, 0x7fff
	v_mov_b32_e32 v29, 0
	v_add3_u32 v14, v10, v11, s13
	v_lshl_add_u64 v[10:11], v[2:3], 0, v[28:29]
	global_store_short_d16_hi v[10:11], v14, off
	s_xor_b64 s[70:71], s[68:69], -1
	v_lshl_add_u64 v[6:7], v[40:41], 0, v[6:7]
	s_cbranch_execz .LBB0_4449

.LBB0_4443:
	v_cndmask_b32_e64 v10, v12, 0, s[68:69]
	v_bfe_u32 v11, v10, 16, 1
	s_movk_i32 s13, 0x7fff
	v_mov_b32_e32 v29, 0
	v_add3_u32 v14, v10, v11, s13
	v_lshl_add_u64 v[10:11], v[2:3], 0, v[28:29]
	global_store_short_d16_hi v[10:11], v14, off offset:32
	s_cbranch_execz .LBB0_4453

.LBB0_4445:
	v_cndmask_b32_e64 v10, v8, 0, s[68:69]
	v_bfe_u32 v11, v10, 16, 1
	s_movk_i32 s13, 0x7fff
	v_mov_b32_e32 v29, 0
	v_add3_u32 v12, v10, v11, s13
	v_lshl_add_u64 v[10:11], v[2:3], 0, v[28:29]
	global_store_short_d16_hi v[10:11], v12, off offset:64
	s_cbranch_execz .LBB0_4457

.LBB0_4447:
	v_cndmask_b32_e64 v8, v4, 0, s[68:69]
	v_bfe_u32 v10, v8, 16, 1
	s_movk_i32 s13, 0x7fff
	v_mov_b32_e32 v29, 0
	v_add3_u32 v8, v8, v10, s13
	v_lshl_add_u64 v[2:3], v[2:3], 0, v[28:29]
	global_store_short_d16_hi v[2:3], v8, off offset:96
	s_cbranch_execnz .LBB0_4464
	s_branch .LBB0_4461

.LBB0_4449:
	s_and_saveexec_b64 s[72:73], s[70:71]
	s_cbranch_execz .LBB0_4451
	v_mov_b32_e32 v27, 0
	v_lshl_add_u64 v[10:11], v[6:7], 0, v[26:27]
	global_store_dword v[10:11], v16, off

.LBB0_4453:
	s_and_saveexec_b64 s[72:73], s[70:71]
	s_cbranch_execz .LBB0_4455
	v_mov_b32_e32 v27, 0
	v_lshl_add_u64 v[10:11], v[6:7], 0, v[26:27]
	global_store_dword v[10:11], v12, off offset:64

.LBB0_4457:
	s_and_saveexec_b64 s[72:73], s[70:71]
	s_cbranch_execz .LBB0_4459
	v_mov_b32_e32 v27, 0
	v_lshl_add_u64 v[10:11], v[6:7], 0, v[26:27]
	global_store_dword v[10:11], v8, off offset:128

.LBB0_4461:
	s_and_saveexec_b64 s[68:69], s[70:71]
	s_cbranch_execz .LBB0_4463
	v_mov_b32_e32 v27, 0
	v_lshl_add_u64 v[2:3], v[6:7], 0, v[26:27]
	global_store_dword v[2:3], v4, off offset:192

.LBB0_4464:
	v_or_b32_e32 v2, 3, v131
	v_ashrrev_i32_e32 v6, 1, v2
	s_movk_i32 s13, 0xfd
	v_cmp_lt_i32_e32 vcc, s13, v2
	v_add_u32_e32 v2, s27, v6
	v_ashrrev_i32_e32 v3, 31, v2
	v_lshlrev_b64 v[2:3], 8, v[2:3]
	v_ashrrev_i32_e32 v7, 31, v6
	v_lshl_add_u64 v[2:3], s[66:67], 0, v[2:3]
	v_lshlrev_b64 v[6:7], 9, v[6:7]
	s_and_b64 s[68:69], s[14:15], vcc
	s_mov_b64 s[72:73], -1
	v_lshl_add_u64 v[2:3], v[2:3], 0, s[28:29]
	v_lshl_add_u64 v[6:7], v[42:43], 0, v[6:7]
	s_and_b64 vcc, exec, s[6:7]
	s_cbranch_vccnz .LBB0_4472
	v_cndmask_b32_e64 v4, v17, 0, s[68:69]
	v_bfe_u32 v8, v4, 16, 1
	s_movk_i32 s13, 0x7fff
	v_mov_b32_e32 v29, 0
	v_add3_u32 v4, v4, v8, s13
	v_lshl_add_u64 v[10:11], v[2:3], 0, v[28:29]
	global_store_short_d16_hi v[10:11], v4, off
	s_xor_b64 s[70:71], s[68:69], -1
	v_lshl_add_u64 v[6:7], v[6:7], 0, s[74:75]
	s_cbranch_execz .LBB0_4473

.LBB0_4467:
	v_cndmask_b32_e64 v4, v13, 0, s[68:69]
	v_bfe_u32 v8, v4, 16, 1
	s_movk_i32 s13, 0x7fff
	v_mov_b32_e32 v31, 0
	v_add3_u32 v4, v4, v8, s13
	v_lshl_add_u64 v[10:11], v[2:3], 0, v[30:31]
	global_store_short_d16_hi v[10:11], v4, off
	s_cbranch_execz .LBB0_4477

.LBB0_4469:
	v_cndmask_b32_e64 v4, v9, 0, s[68:69]
	v_bfe_u32 v8, v4, 16, 1
	s_movk_i32 s13, 0x7fff
	v_mov_b32_e32 v33, 0
	v_add3_u32 v4, v4, v8, s13
	v_lshl_add_u64 v[10:11], v[2:3], 0, v[32:33]
	global_store_short_d16_hi v[10:11], v4, off
	s_cbranch_execz .LBB0_4481

.LBB0_4471:
	v_cndmask_b32_e64 v4, v5, 0, s[68:69]
	v_bfe_u32 v8, v4, 16, 1
	s_movk_i32 s13, 0x7fff
	v_mov_b32_e32 v35, 0
	v_add3_u32 v4, v4, v8, s13
	v_lshl_add_u64 v[2:3], v[2:3], 0, v[34:35]
	global_store_short_d16_hi v[2:3], v4, off
	s_cbranch_execnz .LBB0_4488
	s_branch .LBB0_4485

.LBB0_4473:
	s_and_saveexec_b64 s[72:73], s[70:71]
	s_cbranch_execz .LBB0_4475
	v_mov_b32_e32 v27, 0
	v_lshl_add_u64 v[10:11], v[6:7], 0, v[26:27]
	global_store_dword v[10:11], v17, off

.LBB0_4477:
	s_and_saveexec_b64 s[72:73], s[70:71]
	s_cbranch_execz .LBB0_4479
	v_lshlrev_b32_e32 v10, 2, v109
	v_mov_b32_e32 v11, 0
	v_lshl_add_u64 v[10:11], v[6:7], 0, v[10:11]
	global_store_dword v[10:11], v13, off

.LBB0_4481:
	s_and_saveexec_b64 s[72:73], s[70:71]
	s_cbranch_execz .LBB0_4483
	v_lshlrev_b32_e32 v10, 2, v110
	v_mov_b32_e32 v11, 0
	v_lshl_add_u64 v[10:11], v[6:7], 0, v[10:11]
	global_store_dword v[10:11], v9, off

.LBB0_4485:
	s_and_saveexec_b64 s[68:69], s[70:71]
	s_cbranch_execz .LBB0_4487
	v_lshlrev_b32_e32 v2, 2, v111
	v_mov_b32_e32 v3, 0
	v_lshl_add_u64 v[2:3], v[6:7], 0, v[2:3]
	global_store_dword v[2:3], v5, off

.LBB0_4551:
	v_add_u32_e32 v29, s13, v114
	ds_read2_b32 v[36:37], v27 offset1:16
	ds_read2_b32 v[38:39], v29 offset1:4
	v_add_u32_e32 v31, 0x400, v27
	s_add_i32 s13, s13, 64
	s_cmpk_lg_i32 s13, 0x200
	s_waitcnt lgkmcnt(0)
	v_mfma_f32_16x16x4_f32 v[14:17], v38, v36, v[14:17]
	v_mfma_f32_16x16x4_f32 v[10:13], v38, v37, v[10:13]
	ds_read2_b32 v[36:37], v27 offset0:32 offset1:48
	s_waitcnt lgkmcnt(0)
	v_mfma_f32_16x16x4_f32 v[6:9], v38, v36, v[6:9]
	v_mfma_f32_16x16x4_f32 v[2:5], v38, v37, v[2:5]
	ds_read2_b32 v[36:37], v31 offset1:16
	s_waitcnt lgkmcnt(0)
	v_mfma_f32_16x16x4_f32 v[14:17], v39, v36, v[14:17]
	v_mfma_f32_16x16x4_f32 v[10:13], v39, v37, v[10:13]
	ds_read2_b32 v[36:37], v31 offset0:32 offset1:48
	v_add_u32_e32 v31, 0x800, v27
	s_waitcnt lgkmcnt(0)
	v_mfma_f32_16x16x4_f32 v[6:9], v39, v36, v[6:9]
	v_mfma_f32_16x16x4_f32 v[2:5], v39, v37, v[2:5]
	ds_read2_b32 v[36:37], v29 offset0:8 offset1:12
	ds_read2_b32 v[38:39], v31 offset1:16
	v_add_u32_e32 v29, 0xc00, v27
	v_add_u32_e32 v27, 0x1000, v27
	s_waitcnt lgkmcnt(0)
	v_mfma_f32_16x16x4_f32 v[14:17], v36, v38, v[14:17]
	v_mfma_f32_16x16x4_f32 v[10:13], v36, v39, v[10:13]
	ds_read2_b32 v[38:39], v31 offset0:32 offset1:48
	s_waitcnt lgkmcnt(0)
	v_mfma_f32_16x16x4_f32 v[6:9], v36, v38, v[6:9]
	v_mfma_f32_16x16x4_f32 v[2:5], v36, v39, v[2:5]
	ds_read2_b32 v[38:39], v29 offset1:16
	s_waitcnt lgkmcnt(0)
	v_mfma_f32_16x16x4_f32 v[14:17], v37, v38, v[14:17]
	v_mfma_f32_16x16x4_f32 v[10:13], v37, v39, v[10:13]
	ds_read2_b32 v[38:39], v29 offset0:32 offset1:48
	s_waitcnt lgkmcnt(0)
	v_mfma_f32_16x16x4_f32 v[6:9], v37, v38, v[6:9]
	v_mfma_f32_16x16x4_f32 v[2:5], v37, v39, v[2:5]
	s_cbranch_scc1 .LBB0_4551
	v_add_u32_e32 v115, s12, v112
	v_ashrrev_i32_e32 v38, 1, v115
	v_add_u32_e32 v36, s27, v38
	s_waitcnt lgkmcnt(0)
	s_movk_i32 s12, 0xfd
	v_ashrrev_i32_e32 v37, 31, v36
	v_cmp_lt_i32_e32 vcc, s12, v115
	v_lshlrev_b64 v[36:37], 8, v[36:37]
	v_ashrrev_i32_e32 v39, 31, v38
	s_and_b64 s[12:13], s[14:15], vcc
	s_mov_b64 s[18:19], -1
	v_lshl_add_u64 v[44:45], s[64:65], 0, v[36:37]
	s_and_b64 vcc, exec, s[6:7]
	v_lshlrev_b64 v[38:39], 9, v[38:39]
	s_cbranch_vccnz .LBB0_4560
	v_cndmask_b32_e64 v27, v14, 0, s[12:13]
	v_bfe_u32 v29, v27, 16, 1
	s_movk_i32 s16, 0x7fff
	v_add3_u32 v27, v27, v29, s16
	v_mov_b32_e32 v29, 0
	v_lshl_add_u64 v[46:47], v[44:45], 0, v[28:29]
	global_store_short_d16_hi v[46:47], v27, off
	s_xor_b64 s[16:17], s[12:13], -1
	v_lshl_add_u64 v[46:47], v[40:41], 0, v[38:39]
	s_cbranch_execz .LBB0_4561

.LBB0_4600:
	v_or_b32_e32 v2, 2, v115
	v_ashrrev_i32_e32 v6, 1, v2
	s_movk_i32 s12, 0xfd
	v_cmp_lt_i32_e32 vcc, s12, v2
	v_add_u32_e32 v2, s27, v6
	v_ashrrev_i32_e32 v3, 31, v2
	v_lshlrev_b64 v[2:3], 8, v[2:3]
	v_ashrrev_i32_e32 v7, 31, v6
	s_and_b64 s[12:13], s[14:15], vcc
	s_mov_b64 s[18:19], -1
	v_lshl_add_u64 v[2:3], s[64:65], 0, v[2:3]
	s_and_b64 vcc, exec, s[6:7]
	v_lshlrev_b64 v[6:7], 9, v[6:7]
	s_cbranch_vccnz .LBB0_4608
	v_cndmask_b32_e64 v10, v16, 0, s[12:13]
	v_bfe_u32 v11, v10, 16, 1
	s_movk_i32 s16, 0x7fff
	v_mov_b32_e32 v29, 0
	v_add3_u32 v14, v10, v11, s16
	v_lshl_add_u64 v[10:11], v[2:3], 0, v[28:29]
	global_store_short_d16_hi v[10:11], v14, off
	s_xor_b64 s[16:17], s[12:13], -1
	v_lshl_add_u64 v[6:7], v[40:41], 0, v[6:7]
	s_cbranch_execz .LBB0_4609

.LBB0_4624:
	v_or_b32_e32 v2, 3, v115
	v_ashrrev_i32_e32 v6, 1, v2
	s_movk_i32 s12, 0xfd
	v_cmp_lt_i32_e32 vcc, s12, v2
	v_add_u32_e32 v2, s27, v6
	v_ashrrev_i32_e32 v3, 31, v2
	v_lshlrev_b64 v[2:3], 8, v[2:3]
	v_ashrrev_i32_e32 v7, 31, v6
	s_and_b64 s[12:13], s[14:15], vcc
	v_lshl_add_u64 v[2:3], s[66:67], 0, v[2:3]
	s_mov_b64 s[14:15], 0x28800080
	v_lshlrev_b64 v[6:7], 9, v[6:7]
	s_mov_b64 s[16:17], -1
	v_lshl_add_u64 v[2:3], v[2:3], 0, s[14:15]
	v_lshl_add_u64 v[6:7], v[42:43], 0, v[6:7]
	s_and_b64 vcc, exec, s[6:7]
	s_mov_b64 s[18:19], 0x6600100
	s_cbranch_vccnz .LBB0_4632
	v_cndmask_b32_e64 v4, v17, 0, s[12:13]
	v_bfe_u32 v8, v4, 16, 1
	s_movk_i32 s14, 0x7fff
	v_mov_b32_e32 v29, 0
	v_add3_u32 v4, v4, v8, s14
	v_lshl_add_u64 v[10:11], v[2:3], 0, v[28:29]
	global_store_short_d16_hi v[10:11], v4, off
	s_xor_b64 s[14:15], s[12:13], -1
	v_lshl_add_u64 v[6:7], v[6:7], 0, s[18:19]
	s_cbranch_execz .LBB0_4633

.LBB0_4648:
	s_bfe_u32 s6, s40, 0x30001
	s_cmp_eq_u32 s6, s96
	s_cselect_b64 s[12:13], -1, 0
	s_cmp_lg_u32 s6, s96
	s_cbranch_scc1 .LBB0_4650
	s_ashr_i32 s6, s40, 4
	s_lshr_b32 s7, s40, 1
	s_and_b32 s14, s6, -2
	s_or_b32 s6, s14, s26
	s_lshl_b32 s7, s7, 4
	s_addk_i32 s6, 0x100
	s_and_b32 s8, s7, 0xf0
	s_cmpk_gt_i32 s14, 0xff0e
	s_cselect_b64 s[14:15], -1, 0
	s_and_b32 s7, s40, 0x60
	s_cmpk_eq_i32 s7, 0x60
	s_cselect_b64 s[16:17], -1, 0
	s_ashr_i32 s7, s6, 31
	s_or_b64 s[14:15], s[16:17], s[14:15]
	s_lshl_b64 s[16:17], s[6:7], 18
	s_add_u32 s2, s2, s16
	s_addc_u32 s3, s3, s17
	s_add_u32 s19, s2, 0x80000
	s_addc_u32 s20, s3, 0
	s_lshl_b32 s7, s8, 10
	s_add_u32 s16, s2, s7
	s_addc_u32 s17, s3, 0
	s_add_u32 s7, s2, 0x80400
	s_addc_u32 s18, s3, 0
	s_add_u32 s22, s16, 0x1000
	s_addc_u32 s23, s17, 0
	s_add_u32 s24, s16, 0x1400
	s_addc_u32 s25, s17, 0
	v_add_u32_e32 v2, 64, v132
	v_mov_b32_e32 v3, 0
	s_add_u32 s26, s16, 0x1800
	v_lshl_add_u64 v[4:5], s[16:17], 0, v[24:25]
	v_lshl_add_u64 v[6:7], s[22:23], 0, v[24:25]
	s_addc_u32 s27, s17, 0
	v_lshlrev_b64 v[2:3], 2, v[2:3]
	global_load_dword v20, v[4:5], off
	global_load_dword v21, v[4:5], off offset:256
	global_load_dword v22, v[4:5], off offset:2560
	global_load_dword v23, v[4:5], off offset:2816
	global_load_dword v107, v[4:5], off offset:1024
	global_load_dword v105, v[4:5], off offset:1280
	global_load_dword v103, v[4:5], off offset:2048
	global_load_dword v100, v[4:5], off offset:2304
	v_lshl_add_u64 v[8:9], s[24:25], 0, v[24:25]
	global_load_dword v108, v[4:5], off offset:3584
	global_load_dword v106, v[4:5], off offset:3840
	global_load_dword v104, v[6:7], off offset:512
	global_load_dword v102, v[6:7], off offset:768
	global_load_dword v98, v[4:5], off offset:3072
	global_load_dword v90, v[8:9], off
	global_load_dword v94, v[6:7], off
	global_load_dword v97, v[4:5], off offset:3328
	v_lshl_add_u64 v[6:7], s[22:23], 0, v[2:3]
	s_add_u32 s22, s16, 0x1c00
	s_addc_u32 s23, s17, 0
	v_lshl_add_u64 v[12:13], s[24:25], 0, v[2:3]
	s_add_u32 s24, s16, 0x2000
	s_addc_u32 s25, s17, 0
	v_lshl_add_u64 v[10:11], s[26:27], 0, v[24:25]
	v_lshl_add_u64 v[14:15], s[22:23], 0, v[24:25]
	global_load_dword v101, v[8:9], off offset:512
	global_load_dword v99, v[8:9], off offset:768
	global_load_dword v93, v[6:7], off
	global_load_dword v96, v[10:11], off offset:512
	global_load_dword v95, v[10:11], off offset:768
	global_load_dword v89, v[12:13], off
	global_load_dword v82, v[14:15], off
	global_load_dword v87, v[10:11], off
	v_lshl_add_u64 v[6:7], s[26:27], 0, v[2:3]
	s_add_u32 s26, s16, 0x2400
	s_addc_u32 s27, s17, 0
	v_lshl_add_u64 v[10:11], s[22:23], 0, v[2:3]
	s_add_u32 s22, s16, 0x2800
	s_addc_u32 s23, s17, 0
	v_lshl_add_u64 v[8:9], s[24:25], 0, v[24:25]
	v_lshl_add_u64 v[12:13], s[26:27], 0, v[24:25]
	global_load_dword v92, v[14:15], off offset:512
	global_load_dword v91, v[14:15], off offset:768
	global_load_dword v85, v[6:7], off
	global_load_dword v88, v[8:9], off offset:512
	global_load_dword v86, v[8:9], off offset:768
	global_load_dword v81, v[10:11], off
	global_load_dword v73, v[12:13], off
	global_load_dword v79, v[8:9], off
	v_lshl_add_u64 v[6:7], s[24:25], 0, v[2:3]
	s_add_u32 s24, s16, 0x2c00
	s_addc_u32 s25, s17, 0
	v_lshl_add_u64 v[10:11], s[26:27], 0, v[2:3]
	s_add_u32 s26, s16, 0x3000
	s_addc_u32 s27, s17, 0
	v_lshl_add_u64 v[8:9], s[22:23], 0, v[24:25]
	v_lshl_add_u64 v[14:15], s[24:25], 0, v[24:25]
	global_load_dword v84, v[12:13], off offset:512
	global_load_dword v83, v[12:13], off offset:768
	global_load_dword v77, v[6:7], off
	global_load_dword v80, v[8:9], off offset:512
	global_load_dword v78, v[8:9], off offset:768
	global_load_dword v72, v[10:11], off
	global_load_dword v65, v[14:15], off
	global_load_dword v70, v[8:9], off
	v_lshl_add_u64 v[6:7], s[22:23], 0, v[2:3]
	s_add_u32 s22, s16, 0x3400
	s_addc_u32 s23, s17, 0
	v_lshl_add_u64 v[10:11], s[24:25], 0, v[2:3]
	s_add_u32 s24, s16, 0x3800
	s_addc_u32 s25, s17, 0
	v_lshl_add_u64 v[8:9], s[26:27], 0, v[24:25]
	v_lshl_add_u64 v[12:13], s[22:23], 0, v[24:25]
	global_load_dword v75, v[14:15], off offset:512
	global_load_dword v74, v[14:15], off offset:768
	global_load_dword v68, v[6:7], off
	global_load_dword v71, v[8:9], off offset:512
	global_load_dword v69, v[8:9], off offset:768
	global_load_dword v64, v[10:11], off
	global_load_dword v56, v[12:13], off
	global_load_dword v62, v[8:9], off
	v_lshl_add_u64 v[10:11], s[22:23], 0, v[2:3]
	s_mov_b64 s[22:23], 0x3c00
	s_add_u32 s21, s16, 0x4000
	v_lshl_add_u64 v[14:15], v[4:5], 0, s[22:23]
	s_addc_u32 s22, s17, 0
	s_and_b64 s[16:17], s[14:15], exec
	s_cselect_b32 s16, s24, s19
	s_cselect_b32 s17, s25, s20
	s_cmpk_eq_i32 s8, 0xf0
	v_lshl_add_u64 v[6:7], s[26:27], 0, v[2:3]
	s_cselect_b32 s17, s17, s22
	s_cselect_b32 s16, s16, s21
	v_lshl_add_u64 v[2:3], s[24:25], 0, v[2:3]
	v_lshl_add_u64 v[8:9], s[24:25], 0, v[24:25]
	global_load_dword v67, v[12:13], off offset:512
	global_load_dword v66, v[12:13], off offset:768
	global_load_dword v60, v[6:7], off
	global_load_dword v63, v[8:9], off offset:512
	global_load_dword v61, v[8:9], off offset:768
	global_load_dword v55, v[10:11], off
	global_load_dword v58, v[14:15], off offset:512
	global_load_dword v53, v[8:9], off
	global_load_dword v57, v[14:15], off offset:768
	global_load_dword v51, v[2:3], off
	v_lshl_add_u64 v[2:3], s[16:17], 0, v[24:25]
	s_or_b32 s16, s8, 15
	s_lshl_b32 s17, s16, 10
	s_add_u32 s2, s2, s17
	s_addc_u32 s3, s3, 0
	s_add_u32 s17, s2, 0x800
	s_addc_u32 s19, s3, 0
	s_and_b64 s[14:15], s[14:15], exec
	global_load_dword v54, v[2:3], off offset:512
	global_load_dword v52, v[2:3], off offset:768
	s_cselect_b32 s7, s2, s7
	s_cselect_b32 s14, s3, s18
	s_cmpk_lt_u32 s16, 0xfe
	v_add_co_u32_e32 v2, vcc, 0x3000, v4
	s_cselect_b32 s15, s19, s14
	s_cselect_b32 s14, s17, s7
	v_addc_co_u32_e32 v3, vcc, 0, v5, vcc
	v_lshl_add_u64 v[4:5], s[2:3], 0, v[24:25]
	global_load_dword v49, v[2:3], off offset:3072
	global_load_dword v1, v[4:5], off offset:256
	v_lshl_add_u64 v[2:3], s[14:15], 0, v[24:25]
	global_load_dword v50, v[2:3], off offset:512
	global_load_dword v48, v[2:3], off offset:768
	s_andn2_b64 vcc, exec, s[12:13]
	s_cbranch_vccz .LBB0_4651
	s_branch .LBB0_4811

.LBB0_4714:
	v_add_u32_e32 v1, s7, v114
	ds_read2_b32 v[18:19], v113 offset1:16
	ds_read2_b32 v[20:21], v1 offset1:4
	v_add_u32_e32 v22, 0x800, v113
	s_add_i32 s7, s7, 64
	s_cmpk_lg_i32 s7, 0x200
	s_waitcnt lgkmcnt(0)
	v_mfma_f32_16x16x4_f32 v[14:17], v20, v18, v[14:17]
	v_mfma_f32_16x16x4_f32 v[10:13], v20, v19, v[10:13]
	ds_read2_b32 v[18:19], v113 offset0:32 offset1:48
	s_waitcnt lgkmcnt(0)
	v_mfma_f32_16x16x4_f32 v[6:9], v20, v18, v[6:9]
	v_mfma_f32_16x16x4_f32 v[2:5], v20, v19, v[2:5]
	v_add_u32_e32 v20, 0x400, v113
	ds_read2_b32 v[18:19], v20 offset1:16
	s_waitcnt lgkmcnt(0)
	v_mfma_f32_16x16x4_f32 v[14:17], v21, v18, v[14:17]
	v_mfma_f32_16x16x4_f32 v[10:13], v21, v19, v[10:13]
	ds_read2_b32 v[18:19], v20 offset0:32 offset1:48
	s_waitcnt lgkmcnt(0)
	v_mfma_f32_16x16x4_f32 v[6:9], v21, v18, v[6:9]
	v_mfma_f32_16x16x4_f32 v[2:5], v21, v19, v[2:5]
	ds_read2_b32 v[18:19], v1 offset0:8 offset1:12
	ds_read2_b32 v[20:21], v22 offset1:16
	v_add_u32_e32 v1, 0xc00, v113
	v_add_u32_e32 v113, 0x1000, v113
	s_waitcnt lgkmcnt(0)
	v_mfma_f32_16x16x4_f32 v[14:17], v18, v20, v[14:17]
	v_mfma_f32_16x16x4_f32 v[10:13], v18, v21, v[10:13]
	ds_read2_b32 v[20:21], v22 offset0:32 offset1:48
	s_waitcnt lgkmcnt(0)
	v_mfma_f32_16x16x4_f32 v[6:9], v18, v20, v[6:9]
	v_mfma_f32_16x16x4_f32 v[2:5], v18, v21, v[2:5]
	ds_read2_b32 v[20:21], v1 offset1:16
	s_waitcnt lgkmcnt(0)
	v_mfma_f32_16x16x4_f32 v[14:17], v19, v20, v[14:17]
	v_mfma_f32_16x16x4_f32 v[10:13], v19, v21, v[10:13]
	ds_read2_b32 v[20:21], v1 offset0:32 offset1:48
	s_waitcnt lgkmcnt(0)
	v_mfma_f32_16x16x4_f32 v[6:9], v19, v20, v[6:9]
	v_mfma_f32_16x16x4_f32 v[2:5], v19, v21, v[2:5]
	s_cbranch_scc1 .LBB0_4714
	s_ashr_i32 s6, s6, 3
	s_lshl_b32 s3, s3, 7
	s_ashr_i32 s7, s6, 31
	v_add_u32_e32 v1, s8, v112
	s_add_u32 s6, s6, s4
	v_add3_u32 v38, s2, -8, v59
	s_movk_i32 s2, 0xfd
	s_addc_u32 s7, s7, 0
	v_ashrrev_i32_e32 v24, 1, v1
	v_cmp_lt_i32_e32 vcc, s2, v1
	s_lshl_b64 s[16:17], s[6:7], 17
	s_and_b64 s[18:19], vcc, s[12:13]
	v_add_u32_e32 v18, s3, v24
	s_waitcnt lgkmcnt(0)
	v_mov_b32_e32 v39, 0
	v_ashrrev_i32_e32 v19, 31, v18
	s_add_u32 s8, s5, s16
	v_lshlrev_b64 v[20:21], 16, v[38:39]
	s_addc_u32 s9, s9, s17
	v_lshlrev_b64 v[22:23], 8, v[18:19]
	v_ashrrev_i32_e32 v25, 31, v24
	v_cndmask_b32_e64 v27, 0, 1, s[14:15]
	s_mov_b64 s[20:21], -1
	v_lshl_add_u64 v[36:37], s[8:9], 0, v[22:23]
	v_lshl_add_u64 v[18:19], s[10:11], 0, v[20:21]
	v_cmp_ne_u32_e64 s[6:7], 1, v27
	s_andn2_b64 vcc, exec, s[14:15]
	v_lshlrev_b64 v[24:25], 9, v[24:25]
	s_cbranch_vccnz .LBB0_4723
	v_cndmask_b32_e64 v27, v14, 0, s[18:19]
	v_bfe_u32 v29, v27, 16, 1
	s_movk_i32 s2, 0x7fff
	v_add3_u32 v27, v27, v29, s2
	v_mov_b32_e32 v29, v39
	v_lshl_add_u64 v[38:39], v[36:37], 0, v[28:29]
	global_store_short_d16_hi v[38:39], v27, off
	s_xor_b64 s[10:11], s[18:19], -1
	v_lshl_add_u64 v[38:39], v[18:19], 0, v[24:25]
	s_cbranch_execz .LBB0_4724

.LBB0_4869:
	v_lshl_add_u64 v[10:11], s[38:39], 0, v[8:9]
	v_add_co_u32_e32 v14, vcc, 0x22400000, v10
	v_lshl_add_u64 v[12:13], s[38:39], 0, v[6:7]
	s_nop 0
	v_addc_co_u32_e32 v15, vcc, 0, v11, vcc
	v_add_co_u32_e32 v12, vcc, 0x26400000, v12
	global_load_dword v3, v[14:15], off
	s_nop 0
	v_addc_co_u32_e32 v13, vcc, 0, v13, vcc
	v_add_co_u32_e32 v14, vcc, 0x22408000, v10
	global_load_dword v5, v[12:13], off
	global_load_dword v40, v[12:13], off offset:256
	global_load_dword v41, v[12:13], off offset:512
	global_load_dword v42, v[12:13], off offset:768
	global_load_dword v43, v[12:13], off offset:1024
	global_load_dword v44, v[12:13], off offset:1280
	global_load_dword v45, v[12:13], off offset:1536
	global_load_dword v46, v[12:13], off offset:1792
	global_load_dword v47, v[12:13], off offset:2048
	global_load_dword v48, v[12:13], off offset:2304
	global_load_dword v49, v[12:13], off offset:2560
	global_load_dword v50, v[12:13], off offset:2816
	global_load_dword v51, v[12:13], off offset:3072
	global_load_dword v52, v[12:13], off offset:3328
	global_load_dword v53, v[12:13], off offset:3584
	v_addc_co_u32_e32 v15, vcc, 0, v11, vcc
	v_add_co_u32_e32 v16, vcc, 0x22410000, v10
	s_add_i32 s2, s2, 16
	s_nop 0
	v_addc_co_u32_e32 v17, vcc, 0, v11, vcc
	v_add_co_u32_e32 v18, vcc, 0x22418000, v10
	global_load_dword v54, v[14:15], off
	global_load_dword v55, v[16:17], off
	v_addc_co_u32_e32 v19, vcc, 0, v11, vcc
	v_add_co_u32_e32 v14, vcc, 0x22420000, v10
	v_lshl_add_u64 v[6:7], v[6:7], 0, s[8:9]
	s_nop 0
	v_addc_co_u32_e32 v15, vcc, 0, v11, vcc
	v_add_co_u32_e32 v16, vcc, 0x22428000, v10
	global_load_dword v56, v[18:19], off
	global_load_dword v57, v[14:15], off
	v_addc_co_u32_e32 v17, vcc, 0, v11, vcc
	v_add_co_u32_e32 v14, vcc, 0x22430000, v10
	v_lshl_add_u64 v[8:9], v[8:9], 0, s[10:11]
	s_nop 0
	v_addc_co_u32_e32 v15, vcc, 0, v11, vcc
	v_add_co_u32_e32 v18, vcc, 0x22438000, v10
	global_load_dword v58, v[16:17], off
	global_load_dword v59, v[14:15], off
	v_addc_co_u32_e32 v19, vcc, 0, v11, vcc
	v_add_co_u32_e32 v14, vcc, 0x22440000, v10
	global_load_dword v60, v[18:19], off
	global_load_dword v61, v[12:13], off offset:3840
	v_addc_co_u32_e32 v15, vcc, 0, v11, vcc
	v_add_co_u32_e32 v16, vcc, 0x22448000, v10
	s_cmpk_lt_u32 s2, 0x70
	s_nop 0
	v_addc_co_u32_e32 v17, vcc, 0, v11, vcc
	v_add_co_u32_e32 v12, vcc, 0x22450000, v10
	global_load_dword v62, v[14:15], off
	global_load_dword v63, v[16:17], off
	v_addc_co_u32_e32 v13, vcc, 0, v11, vcc
	v_add_co_u32_e32 v14, vcc, 0x22458000, v10
	s_waitcnt vmcnt(0) lgkmcnt(0)
	v_fmac_f32_e32 v3, v1, v5
	v_addc_co_u32_e32 v15, vcc, 0, v11, vcc
	v_add_co_u32_e32 v16, vcc, 0x22460000, v10
	global_load_dword v64, v[12:13], off
	global_load_dword v65, v[14:15], off
	v_addc_co_u32_e32 v17, vcc, 0, v11, vcc
	v_add_co_u32_e32 v12, vcc, 0x22468000, v10
	v_fmac_f32_e32 v54, v3, v40
	s_nop 0
	v_addc_co_u32_e32 v13, vcc, 0, v11, vcc
	v_add_co_u32_e32 v14, vcc, 0x22470000, v10
	global_load_dword v66, v[16:17], off
	global_load_dword v67, v[12:13], off
	v_addc_co_u32_e32 v15, vcc, 0, v11, vcc
	v_add_co_u32_e32 v12, vcc, 0x22478000, v10
	v_fmac_f32_e32 v55, v54, v41
	s_nop 0
	v_addc_co_u32_e32 v13, vcc, 0, v11, vcc
	global_load_dword v68, v[14:15], off
	global_load_dword v69, v[12:13], off
	v_add_co_u32_e32 v16, vcc, 0x24400000, v10
	v_fmac_f32_e32 v56, v55, v42
	s_nop 0
	v_addc_co_u32_e32 v17, vcc, 0, v11, vcc
	v_add_co_u32_e32 v12, vcc, 0x24408000, v10
	global_store_dword v[16:17], v1, off
	s_nop 0
	v_addc_co_u32_e32 v13, vcc, 0, v11, vcc
	v_add_co_u32_e32 v14, vcc, 0x24410000, v10
	v_fmac_f32_e32 v57, v56, v43
	s_nop 0
	v_addc_co_u32_e32 v15, vcc, 0, v11, vcc
	v_add_co_u32_e32 v16, vcc, 0x24418000, v10
	v_fmac_f32_e32 v58, v57, v44
	s_nop 0
	v_addc_co_u32_e32 v17, vcc, 0, v11, vcc
	v_add_co_u32_e32 v18, vcc, 0x24420000, v10
	v_fmac_f32_e32 v59, v58, v45
	s_nop 0
	v_addc_co_u32_e32 v19, vcc, 0, v11, vcc
	v_add_co_u32_e32 v20, vcc, 0x24428000, v10
	v_fmac_f32_e32 v60, v59, v46
	s_nop 0
	v_addc_co_u32_e32 v21, vcc, 0, v11, vcc
	v_add_co_u32_e32 v22, vcc, 0x24430000, v10
	v_fmac_f32_e32 v62, v60, v47
	s_nop 0
	v_addc_co_u32_e32 v23, vcc, 0, v11, vcc
	v_add_co_u32_e32 v24, vcc, 0x24438000, v10
	v_fmac_f32_e32 v63, v62, v48
	s_nop 0
	v_addc_co_u32_e32 v25, vcc, 0, v11, vcc
	v_add_co_u32_e32 v26, vcc, 0x24440000, v10
	global_store_dword v[12:13], v3, off
	s_nop 0
	v_addc_co_u32_e32 v27, vcc, 0, v11, vcc
	v_add_co_u32_e32 v28, vcc, 0x24448000, v10
	global_store_dword v[14:15], v54, off
	s_nop 0
	v_addc_co_u32_e32 v29, vcc, 0, v11, vcc
	v_add_co_u32_e32 v30, vcc, 0x24450000, v10
	global_store_dword v[16:17], v55, off
	s_nop 0
	v_addc_co_u32_e32 v31, vcc, 0, v11, vcc
	v_add_co_u32_e32 v32, vcc, 0x24458000, v10
	s_waitcnt vmcnt(0) lgkmcnt(0)
	v_fmac_f32_e32 v64, v63, v49
	v_addc_co_u32_e32 v33, vcc, 0, v11, vcc
	v_add_co_u32_e32 v34, vcc, 0x24460000, v10
	v_fmac_f32_e32 v65, v64, v50
	s_nop 0
	v_addc_co_u32_e32 v35, vcc, 0, v11, vcc
	v_add_co_u32_e32 v36, vcc, 0x24468000, v10
	global_store_dword v[18:19], v56, off
	s_nop 0
	v_addc_co_u32_e32 v37, vcc, 0, v11, vcc
	v_add_co_u32_e32 v38, vcc, 0x24470000, v10
	v_fmac_f32_e32 v66, v65, v51
	s_nop 0
	v_addc_co_u32_e32 v39, vcc, 0, v11, vcc
	v_fmac_f32_e32 v67, v66, v52
	v_add_co_u32_e32 v10, vcc, 0x24478000, v10
	v_fmac_f32_e32 v68, v67, v53
	v_mov_b32_e32 v1, v69
	v_addc_co_u32_e32 v11, vcc, 0, v11, vcc
	v_fmac_f32_e32 v1, v68, v61
	global_store_dword v[20:21], v57, off
	global_store_dword v[22:23], v58, off
	global_store_dword v[24:25], v59, off
	global_store_dword v[26:27], v60, off
	global_store_dword v[28:29], v62, off
	global_store_dword v[30:31], v63, off
	global_store_dword v[32:33], v64, off
	global_store_dword v[34:35], v65, off
	global_store_dword v[36:37], v66, off
	global_store_dword v[38:39], v67, off
	global_store_dword v[10:11], v68, off
	s_cbranch_scc1 .LBB0_4869
	v_ashrrev_i32_e32 v5, 31, v4
	v_readlane_b32 s2, v228, 15
	v_lshlrev_b64 v[4:5], 15, v[4:5]
	v_readlane_b32 s3, v228, 16
	v_lshlrev_b32_e32 v2, 2, v2
	v_mov_b32_e32 v3, 0
	v_lshl_add_u64 v[4:5], s[2:3], 0, v[4:5]
	v_lshl_add_u64 v[2:3], v[4:5], 0, v[2:3]
	v_add_co_u32_e32 v2, vcc, 0x82c0000, v2
	s_nop 1
	v_addc_co_u32_e32 v3, vcc, 0, v3, vcc
	global_store_dword v[2:3], v1, off

.LBB0_4876:
	v_mov_b32_e32 v138, v0
	s_cmp_eq_u32 s4, s74
	v_readfirstlane_b32 s86, v138
	s_mov_b64 s[6:7], -1
	s_cbranch_scc1 .LBB0_4890
	s_cmp_gt_u32 s4, s74
	s_cselect_b64 s[6:7], -1, 0
	v_cndmask_b32_e64 v1, 0, 1, s[6:7]
	s_mov_b64 s[68:69], s[66:67]
	v_readfirstlane_b32 s5, v1
	s_cmp_eq_u32 s4, s5
	s_cselect_b32 s5, 0, 0x100
	s_add_i32 s5, s5, s40
	s_cmpk_lt_i32 s5, 0x100
	s_mov_b32 s5, s3
	v_mov_b32_e32 v91, v0
	s_cselect_b32 s65, s75, s76
	v_readfirstlane_b32 s6, v91
	s_ashr_i32 s28, s6, 6
	s_lshl_b32 s52, s65, 6
	s_lshl_b32 s70, s28, 3
	s_add_i32 s6, s70, s52
	v_bfe_u32 v100, v91, 2, 3
	v_or_b32_e32 v96, s6, v100
	v_ashrrev_i32_e32 v97, 31, v96
	v_and_or_b32 v1, v91, 3, s77
	v_lshl_add_u64 v[6:7], s[50:51], 0, v[96:97]
	v_mov_b64_e32 v[2:3], s[68:69]
	s_movk_i32 s8, 0x3000
	v_mad_u64_u32 v[2:3], s[6:7], v6, s8, v[2:3]
	v_mul_u32_u24_e32 v4, 3, v1
	v_mad_i32_i24 v3, v7, s8, v3
	v_lshlrev_b32_e32 v98, 2, v4
	v_lshl_add_u64 v[2:3], v[2:3], 0, v[98:99]
	v_add_co_u32_e32 v2, vcc, 0x16001000, v2
	s_lshl_b32 s29, s28, 13
	s_nop 0
	v_addc_co_u32_e32 v3, vcc, 0, v3, vcc
	global_load_dwordx3 v[2:4], v[2:3], off offset:1024
	v_and_b32_e32 v139, 63, v91
	s_add_i32 s42, s29, 0x9000
	v_and_b32_e32 v114, 31, v91
	v_lshl_or_b32 v5, v139, 2, s42
	v_or_b32_e32 v8, 0xffffffc0, v139
	s_mov_b64 s[6:7], 0
.LBB0_4878:
	v_add_u32_e32 v8, 64, v8
	s_movk_i32 s8, 0x7bf
	v_cmp_lt_u32_e32 vcc, s8, v8
	v_add_u32_e32 v9, s5, v5
	v_add_u32_e32 v5, 0x100, v5
	s_or_b64 s[6:7], vcc, s[6:7]
	ds_write_b32 v9, v99
	s_andn2_b64 exec, exec, s[6:7]
	s_cbranch_execnz .LBB0_4878
	s_or_b64 exec, exec, s[6:7]
	s_add_u32 s6, s68, s78
	s_addc_u32 s7, s69, 0
	s_lshl_b32 s49, s79, 1
	s_add_u32 s6, s6, s49
	v_lshlrev_b64 v[6:7], 10, v[6:7]
	s_addc_u32 s7, s7, 0
	s_add_u32 s22, s6, 0x28800000
	v_lshl_add_u64 v[6:7], s[68:69], 0, v[6:7]
	v_lshlrev_b32_e32 v98, 7, v1
	s_addc_u32 s23, s7, 0
	v_lshl_add_u64 v[6:7], v[6:7], 0, v[98:99]
	s_mov_b64 s[6:7], 0x26800000
	v_mov_b32_e32 v5, v139
	v_lshl_add_u64 v[94:95], v[6:7], 0, s[6:7]
	s_waitcnt lgkmcnt(0)
	s_ashr_i32 s71, s70, 31
	v_ashrrev_i32_e32 v6, 5, v5
	v_lshlrev_b32_e32 v8, 3, v6
	v_ashrrev_i32_e32 v9, 31, v8
	v_lshl_add_u64 v[8:9], v[8:9], 1, v[94:95]
	global_load_dwordx4 v[34:37], v[8:9], off
	global_load_dwordx4 v[38:41], v[8:9], off offset:32
	global_load_dwordx4 v[42:45], v[8:9], off offset:64
	global_load_dwordx4 v[46:49], v[8:9], off offset:96
	v_min_i32_e32 v8, 0x1ff, v5
	v_ashrrev_i32_e32 v9, 31, v8
	v_lshlrev_b64 v[8:9], 8, v[8:9]
	v_lshl_add_u64 v[8:9], s[22:23], 0, v[8:9]
	v_lshl_add_u64 v[8:9], s[70:71], 1, v[8:9]
	s_waitcnt lgkmcnt(0)
	s_barrier
	global_load_dwordx4 v[50:53], v[8:9], off
	v_add_u32_e32 v1, 1, v1
	v_cvt_f32_ubyte0_e32 v7, v1
	s_mov_b32 s6, 0x42fc0000
	v_cmp_lt_f32_e32 vcc, s6, v7
	s_lshl_b32 s6, s28, 10
	s_add_i32 s85, s5, s6
	v_lshlrev_b32_e32 v1, 4, v5
	s_cmp_gt_u32 s65, 15
	v_cndmask_b32_e32 v8, 0, v126, vcc
	v_cndmask_b32_e32 v9, 0, v131, vcc
	v_add_u32_e32 v64, s85, v1
	s_cselect_b64 s[24:25], -1, 0
	s_cmp_lt_u32 s65, 16
	s_waitcnt vmcnt(0) lgkmcnt(0)
	ds_write_b128 v64, v[50:53]
	s_waitcnt lgkmcnt(0)
	s_barrier
	s_cbranch_scc1 .LBB0_4881
	v_min_i32_e32 v10, 0x1bf, v5
	v_ashrrev_i32_e32 v11, 31, v10
	v_lshlrev_b64 v[10:11], 8, v[10:11]
	v_lshl_add_u64 v[10:11], s[22:23], 0, v[10:11]
	v_lshl_add_u64 v[10:11], s[70:71], 1, v[10:11]
	v_add_co_u32_e32 v10, vcc, 0x4000, v10
	s_nop 1
	v_addc_co_u32_e32 v11, vcc, 0, v11, vcc
	global_load_dwordx4 v[50:53], v[10:11], off

.LBB0_4882:
	s_and_b32 s46, s31, 0x2000
	v_add_u32_e32 v58, s46, v66
	ds_read_b128 v[2:5], v58
	ds_read_b128 v[54:57], v58 offset:2048
	ds_read_b128 v[230:233], v58 offset:512
	ds_read_b128 v[234:237], v58 offset:2560
	ds_read_b128 v[238:241], v58 offset:4096
	ds_read_b128 v[242:245], v58 offset:4608
	ds_read_b128 v[246:249], v58 offset:6144
	ds_read_b128 v[250:253], v58 offset:6656
	s_waitcnt lgkmcnt(6)
	v_mfma_f32_32x32x16_bf16 v[18:33], v[2:5], v[34:37], 0
	v_mfma_f32_32x32x16_bf16 v[18:33], v[54:57], v[38:41], v[18:33]
	s_waitcnt lgkmcnt(4)
	v_mfma_f32_32x32x16_bf16 v[2:17], v[230:233], v[34:37], 0
	v_mfma_f32_32x32x16_bf16 v[2:17], v[234:237], v[38:41], v[2:17]
	s_waitcnt lgkmcnt(3)
	v_mfma_f32_32x32x16_bf16 v[18:33], v[238:241], v[42:45], v[18:33]
	s_waitcnt lgkmcnt(2)
	v_mfma_f32_32x32x16_bf16 v[2:17], v[242:245], v[42:45], v[2:17]
	s_waitcnt lgkmcnt(1)
	v_mfma_f32_32x32x16_bf16 v[18:33], v[246:249], v[46:49], v[18:33]
	s_waitcnt lgkmcnt(0)
	v_mfma_f32_32x32x16_bf16 v[2:17], v[250:253], v[46:49], v[2:17]
	v_cvt_f32_i32_e32 v54, v70
	v_cmp_lt_i32_e64 s[20:21], 62, v71
	s_cmp_eq_u64 s[20:21], exec
	v_fma_f32 v73, v90, v54, v65
	v_add_f32_e32 v56, v120, v73
	v_add_f32_e32 v57, v92, v56
	v_add_f32_e32 v74, v119, v73
	s_nop 1
	v_pk_add_f32 v[54:55], v[56:57], v[18:19]
	v_pk_add_f32 v[18:19], v[102:103], v[56:57] op_sel_hi:[1,0]
	s_nop 0
	v_pk_add_f32 v[18:19], v[18:19], v[20:21]
	v_add_f32_e32 v20, v120, v74
	v_add_f32_e32 v21, v92, v20
	v_pk_add_f32 v[62:63], v[20:21], v[2:3]
	v_pk_add_f32 v[2:3], v[102:103], v[20:21] op_sel_hi:[1,0]
	s_nop 0
	v_pk_add_f32 v[58:59], v[2:3], v[4:5]
	v_add_f32_e32 v2, v105, v73
	v_add_f32_e32 v3, v92, v2
	v_pk_add_f32 v[56:57], v[2:3], v[22:23]
	v_pk_add_f32 v[2:3], v[102:103], v[2:3] op_sel_hi:[1,0]
	s_nop 0
	v_pk_add_f32 v[20:21], v[2:3], v[24:25]
	v_add_f32_e32 v2, v105, v74
	v_add_f32_e32 v3, v92, v2
	v_pk_add_f32 v[60:61], v[2:3], v[6:7]
	v_pk_add_f32 v[2:3], v[102:103], v[2:3] op_sel_hi:[1,0]
	v_add_f32_e32 v6, v109, v74
	v_pk_add_f32 v[24:25], v[2:3], v[8:9]
	v_add_f32_e32 v2, v107, v73
	v_add_f32_e32 v3, v92, v2
	v_pk_add_f32 v[22:23], v[2:3], v[26:27]
	v_pk_add_f32 v[2:3], v[102:103], v[2:3] op_sel_hi:[1,0]
	v_add_f32_e32 v7, v92, v6
	v_pk_add_f32 v[4:5], v[2:3], v[28:29]
	v_add_f32_e32 v2, v107, v74
	v_add_f32_e32 v3, v92, v2
	v_pk_add_f32 v[26:27], v[2:3], v[10:11]
	v_pk_add_f32 v[2:3], v[102:103], v[2:3] op_sel_hi:[1,0]
	s_nop 0
	v_pk_add_f32 v[10:11], v[2:3], v[12:13]
	v_add_f32_e32 v2, v109, v73
	v_add_f32_e32 v3, v92, v2
	v_pk_add_f32 v[8:9], v[2:3], v[30:31]
	v_pk_add_f32 v[2:3], v[102:103], v[2:3] op_sel_hi:[1,0]
	v_pk_add_f32 v[12:13], v[6:7], v[14:15]
	v_pk_add_f32 v[6:7], v[102:103], v[6:7] op_sel_hi:[1,0]
	v_pk_add_f32 v[2:3], v[2:3], v[32:33]
	v_pk_add_f32 v[6:7], v[6:7], v[16:17]
	s_cbranch_scc1 .LBB0_4884
	v_add_u32_e32 v14, v69, v71
	v_cmp_gt_i32_e64 s[20:21], 0, v14
	s_or_b64 s[20:21], vcc, s[20:21]
	s_nop 0
	v_cndmask_b32_e64 v54, v54, v132, s[20:21]
	v_cmp_gt_i32_e64 s[20:21], 32, v14
	s_or_b64 s[20:21], s[6:7], s[20:21]
	s_nop 0
	v_cndmask_b32_e64 v62, v62, v132, s[20:21]
	v_cmp_gt_i32_e64 s[20:21], 1, v14
	s_or_b64 s[20:21], vcc, s[20:21]
	s_nop 0
	v_cndmask_b32_e64 v55, v55, v132, s[20:21]
	v_cmp_gt_i32_e64 s[20:21], 33, v14
	s_or_b64 s[20:21], s[6:7], s[20:21]
	s_nop 0
	v_cndmask_b32_e64 v63, v63, v132, s[20:21]
	v_cmp_gt_i32_e64 s[20:21], 2, v14
	s_or_b64 s[20:21], vcc, s[20:21]
	s_nop 0
	v_cndmask_b32_e64 v18, v18, v132, s[20:21]
	v_cmp_gt_i32_e64 s[20:21], 34, v14
	s_or_b64 s[20:21], s[6:7], s[20:21]
	s_nop 0
	v_cndmask_b32_e64 v58, v58, v132, s[20:21]
	v_cmp_gt_i32_e64 s[20:21], 3, v14
	s_or_b64 s[20:21], vcc, s[20:21]
	s_nop 0
	v_cndmask_b32_e64 v19, v19, v132, s[20:21]
	v_cmp_gt_i32_e64 s[20:21], 35, v14
	s_or_b64 s[20:21], s[6:7], s[20:21]
	s_nop 0
	v_cndmask_b32_e64 v59, v59, v132, s[20:21]
	v_cmp_gt_i32_e64 s[20:21], 8, v14
	s_or_b64 s[20:21], s[8:9], s[20:21]
	s_nop 0
	v_cndmask_b32_e64 v56, v56, v132, s[20:21]
	v_cmp_gt_i32_e64 s[20:21], 40, v14
	s_or_b64 s[20:21], s[10:11], s[20:21]
	s_nop 0
	v_cndmask_b32_e64 v60, v60, v132, s[20:21]
	v_cmp_gt_i32_e64 s[20:21], 9, v14
	s_or_b64 s[20:21], s[8:9], s[20:21]
	s_nop 0
	v_cndmask_b32_e64 v57, v57, v132, s[20:21]
	v_cmp_gt_i32_e64 s[20:21], 41, v14
	s_or_b64 s[20:21], s[10:11], s[20:21]
	s_nop 0
	v_cndmask_b32_e64 v61, v61, v132, s[20:21]
	v_cmp_gt_i32_e64 s[20:21], 10, v14
	s_or_b64 s[20:21], s[8:9], s[20:21]
	s_nop 0
	v_cndmask_b32_e64 v20, v20, v132, s[20:21]
	v_cmp_gt_i32_e64 s[20:21], 42, v14
	s_or_b64 s[20:21], s[10:11], s[20:21]
	s_nop 0
	v_cndmask_b32_e64 v24, v24, v132, s[20:21]
	v_cmp_gt_i32_e64 s[20:21], 11, v14
	s_or_b64 s[20:21], s[8:9], s[20:21]
	s_nop 0
	v_cndmask_b32_e64 v21, v21, v132, s[20:21]
	v_cmp_gt_i32_e64 s[20:21], 43, v14
	s_or_b64 s[20:21], s[10:11], s[20:21]
	s_nop 0
	v_cndmask_b32_e64 v25, v25, v132, s[20:21]
	v_cmp_gt_i32_e64 s[20:21], 16, v14
	s_or_b64 s[20:21], s[12:13], s[20:21]
	s_nop 0
	v_cndmask_b32_e64 v22, v22, v132, s[20:21]
	v_cmp_gt_i32_e64 s[20:21], 48, v14
	s_or_b64 s[20:21], s[14:15], s[20:21]
	s_nop 0
	v_cndmask_b32_e64 v26, v26, v132, s[20:21]
	v_cmp_gt_i32_e64 s[20:21], 17, v14
	s_or_b64 s[20:21], s[12:13], s[20:21]
	s_nop 0
	v_cndmask_b32_e64 v23, v23, v132, s[20:21]
	v_cmp_gt_i32_e64 s[20:21], 49, v14
	s_or_b64 s[20:21], s[14:15], s[20:21]
	s_nop 0
	v_cndmask_b32_e64 v27, v27, v132, s[20:21]
	v_cmp_gt_i32_e64 s[20:21], 18, v14
	s_or_b64 s[20:21], s[12:13], s[20:21]
	s_nop 0
	v_cndmask_b32_e64 v4, v4, v132, s[20:21]
	v_cmp_gt_i32_e64 s[20:21], 50, v14
	s_or_b64 s[20:21], s[14:15], s[20:21]
	s_nop 0
	v_cndmask_b32_e64 v10, v10, v132, s[20:21]
	v_cmp_gt_i32_e64 s[20:21], 19, v14
	s_or_b64 s[20:21], s[12:13], s[20:21]
	s_nop 0
	v_cndmask_b32_e64 v5, v5, v132, s[20:21]
	v_cmp_gt_i32_e64 s[20:21], 51, v14
	s_or_b64 s[20:21], s[14:15], s[20:21]
	s_nop 0
	v_cndmask_b32_e64 v11, v11, v132, s[20:21]
	v_cmp_gt_i32_e64 s[20:21], 24, v14
	s_or_b64 s[20:21], s[16:17], s[20:21]
	s_nop 0
	v_cndmask_b32_e64 v8, v8, v132, s[20:21]
	v_cmp_gt_i32_e64 s[20:21], 56, v14
	s_or_b64 s[20:21], s[18:19], s[20:21]
	s_nop 0
	v_cndmask_b32_e64 v12, v12, v132, s[20:21]
	v_cmp_gt_i32_e64 s[20:21], 25, v14
	s_or_b64 s[20:21], s[16:17], s[20:21]
	s_nop 0
	v_cndmask_b32_e64 v9, v9, v132, s[20:21]
	v_cmp_gt_i32_e64 s[20:21], 57, v14
	s_or_b64 s[20:21], s[18:19], s[20:21]
	s_nop 0
	v_cndmask_b32_e64 v13, v13, v132, s[20:21]
	v_cmp_gt_i32_e64 s[20:21], 26, v14
	s_or_b64 s[20:21], s[16:17], s[20:21]
	s_nop 0
	v_cndmask_b32_e64 v2, v2, v132, s[20:21]
	v_cmp_gt_i32_e64 s[20:21], 58, v14
	s_or_b64 s[20:21], s[18:19], s[20:21]
	s_nop 0
	v_cndmask_b32_e64 v6, v6, v132, s[20:21]
	v_cmp_gt_i32_e64 s[20:21], 27, v14
	s_or_b64 s[20:21], s[16:17], s[20:21]
	s_nop 0
	v_cndmask_b32_e64 v3, v3, v132, s[20:21]
	v_cmp_gt_i32_e64 s[20:21], 59, v14
	s_or_b64 s[20:21], s[18:19], s[20:21]
	s_nop 0
	v_cndmask_b32_e64 v7, v7, v132, s[20:21]

.LBB0_4886:
	s_add_i32 s20, s43, 2
	s_cmp_gt_u32 s20, s30
	s_waitcnt lgkmcnt(0)
	s_barrier
	s_cbranch_scc1 .LBB0_4888
	v_min_i32_e32 v16, 0x1ff, v68
	v_ashrrev_i32_e32 v17, 31, v16
	v_lshlrev_b64 v[16:17], 8, v[16:17]
	v_lshl_add_u64 v[16:17], s[26:27], 0, v[16:17]
	s_waitcnt vmcnt(0)
	global_load_dwordx4 v[50:53], v[16:17], off

.LBB0_4890:
	s_and_b64 vcc, exec, s[6:7]
	s_cbranch_vccz .LBB0_5502
	s_add_u32 s5, s66, s83
	s_addc_u32 s6, s67, s82
	s_add_u32 s18, s5, 0x16000000
	s_movk_i32 s5, 0x100
	v_and_b32_e32 v1, 63, v138
	s_addc_u32 s19, s6, 0
	v_cmp_gt_i32_e32 vcc, s5, v138
	s_barrier
	s_and_saveexec_b64 s[6:7], vcc
	s_cbranch_execz .LBB0_4893
	v_and_b32_e32 v2, 0xffffffc0, v138
	v_readlane_b32 s5, v228, 21
	s_nop 1
	v_add_u32_e32 v2, s5, v2
	v_or_b32_e32 v2, v2, v1
	v_ashrrev_i32_e32 v3, 31, v2
	v_lshl_add_u64 v[2:3], v[2:3], 2, s[18:19]
	global_load_dword v2, v[2:3], off
	v_lshl_add_u32 v3, v138, 2, s3
	s_waitcnt vmcnt(0) lgkmcnt(0)
	v_mul_f32_e32 v2, 0x3e000000, v2
	ds_write_b32 v3, v2

.LBB0_4900:
	s_add_u32 s6, s66, s88
	s_addc_u32 s7, s67, s89
	s_lshl_b32 s52, s87, 2
	s_add_u32 s8, s6, s52
	s_addc_u32 s9, s7, 0
	v_lshlrev_b32_e32 v102, 2, v1
	v_mov_b32_e32 v103, v99
	s_lshl_b32 s6, s5, 4
	v_lshl_add_u64 v[2:3], s[8:9], 0, v[102:103]
	s_mov_b64 s[8:9], 0x6600000
	v_lshl_add_u64 v[2:3], v[2:3], 0, s[8:9]
	v_mov_b32_e32 v19, 0
	s_cmp_gt_i32 s5, 7
	v_mov_b32_e32 v10, 0
	s_waitcnt lgkmcnt(0)
	s_barrier
	s_cbranch_scc1 .LBB0_4902
	s_ashr_i32 s7, s6, 31
	s_lshl_b64 s[8:9], s[6:7], 9
	v_lshl_add_u64 v[4:5], v[2:3], 0, s[8:9]
	global_load_dword v10, v[4:5], off

.LBB0_5332:
	v_mov_b64_e32 v[4:5], s[0:1]
	s_waitcnt lgkmcnt(0)
	s_barrier
	global_load_dwordx2 v[2:3], v[4:5], off offset:40 sc0 sc1
	s_waitcnt vmcnt(0)
	global_load_dwordx2 v[10:11], v[4:5], off offset:48 sc0 sc1
	s_waitcnt vmcnt(0)
	global_load_dwordx2 v[4:5], v[4:5], off offset:64 sc0 sc1
	s_waitcnt vmcnt(0)
	s_lshl_b32 s6, s5, 2
	s_add_i32 s6, s3, s6
	v_mov_b32_e32 v6, s6
	v_add_u32_e32 v6, 0xc00, v6
	ds_read2_b32 v[6:7], v6 offset1:8
	s_mov_b64 s[8:9], -1
	s_waitcnt lgkmcnt(0)
	v_cmp_gt_i32_e32 vcc, 32, v6
	v_readfirstlane_b32 s10, v6
	v_readfirstlane_b32 s11, v7
	s_cbranch_vccnz .LBB0_5334
	s_add_u32 s6, s18, 0xc00
	s_addc_u32 s7, s19, 0
	s_mov_b64 s[8:9], 0

.LBB0_5338:
	s_or_b32 s6, s14, 1
	s_ashr_i32 s7, s6, 31
	s_lshl_b32 s26, s10, 6
	s_lshl_b32 s27, s11, 6
	s_add_i32 s28, s14, 0x601
	s_lshl_b64 s[6:7], s[6:7], 10
	v_lshrrev_b32_e32 v100, 4, v1
	s_add_u32 s8, s18, s52
	v_or_b32_e32 v14, s26, v100
	s_addc_u32 s9, s19, 0
	v_or_b32_e32 v17, 4, v14
	s_add_u32 s29, s8, 0xc00
	v_subrev_u32_e32 v12, s26, v17
	v_lshl_add_u64 v[104:105], v[6:7], 0, s[52:53]
	s_addc_u32 s30, s9, 0
	v_lshlrev_b32_e32 v98, 10, v100
	v_ashrrev_i32_e32 v13, 31, v12
	v_lshl_add_u64 v[2:3], v[104:105], 0, v[98:99]
	v_mov_b32_e32 v15, s30
	v_cmp_gt_i32_e32 vcc, s44, v14
	v_mov_b32_e32 v16, s29
	v_lshlrev_b64 v[12:13], 10, v[12:13]
	v_and_b32_e32 v50, 15, v138
	v_cndmask_b32_e32 v3, v15, v3, vcc
	v_cndmask_b32_e32 v2, v16, v2, vcc
	v_lshl_add_u64 v[12:13], v[104:105], 0, v[12:13]
	v_cmp_gt_i32_e32 vcc, s44, v17
	v_lshlrev_b32_e32 v98, 4, v50
	v_lshl_add_u64 v[6:7], v[2:3], 0, v[98:99]
	v_cndmask_b32_e32 v13, v15, v13, vcc
	v_cndmask_b32_e32 v12, v16, v12, vcc
	v_lshl_add_u64 v[12:13], v[12:13], 0, v[98:99]
	v_or_b32_e32 v17, 8, v14
	global_load_dwordx4 v[2:5], v[6:7], off nt
	s_nop 0
	global_load_dwordx4 v[6:9], v[6:7], off offset:512 nt
	s_nop 0
	global_load_dwordx4 v[26:29], v[12:13], off nt
	global_load_dwordx4 v[30:33], v[12:13], off offset:512 nt
	v_subrev_u32_e32 v12, s26, v17
	v_ashrrev_i32_e32 v13, 31, v12
	v_lshlrev_b64 v[12:13], 10, v[12:13]
	v_lshl_add_u64 v[12:13], v[104:105], 0, v[12:13]
	v_cmp_gt_i32_e32 vcc, s44, v17
	v_or_b32_e32 v14, 12, v14
	v_lshl_add_u64 v[108:109], v[42:43], 0, s[52:53]
	v_cndmask_b32_e32 v13, v15, v13, vcc
	v_cndmask_b32_e32 v12, v16, v12, vcc
	v_lshl_add_u64 v[12:13], v[12:13], 0, v[98:99]
	global_load_dwordx4 v[34:37], v[12:13], off nt
	global_load_dwordx4 v[38:41], v[12:13], off offset:512 nt
	v_subrev_u32_e32 v12, s26, v14
	v_ashrrev_i32_e32 v13, 31, v12
	v_lshlrev_b64 v[12:13], 10, v[12:13]
	v_lshl_add_u64 v[12:13], v[104:105], 0, v[12:13]
	v_cmp_gt_i32_e32 vcc, s44, v14
	v_and_b32_e32 v43, 64, v166
	v_xor_b32_e32 v42, 1, v166
	v_cndmask_b32_e32 v13, v15, v13, vcc
	v_cndmask_b32_e32 v12, v16, v12, vcc
	v_lshl_add_u64 v[12:13], v[12:13], 0, v[98:99]
	global_load_dwordx4 v[46:49], v[12:13], off nt
	global_load_dwordx4 v[54:57], v[12:13], off offset:512 nt
	v_add_u32_e32 v43, 64, v43
	v_cmp_lt_i32_e32 vcc, v42, v43
	v_lshl_add_u64 v[10:11], v[10:11], 0, s[56:57]
	v_lshl_add_u64 v[10:11], v[10:11], 0, s[6:7]
	v_cndmask_b32_e32 v42, v166, v42, vcc
	v_lshlrev_b32_e32 v138, 2, v42
	v_xor_b32_e32 v42, 2, v166
	v_cmp_lt_i32_e32 vcc, v42, v43
	v_lshl_add_u64 v[10:11], v[10:11], 0, s[52:53]
	s_mov_b64 s[6:7], 0x4000000
	v_cndmask_b32_e32 v42, v166, v42, vcc
	v_lshlrev_b32_e32 v139, 2, v42
	v_xor_b32_e32 v42, 4, v166
	v_cmp_lt_i32_e32 vcc, v42, v43
	v_lshlrev_b32_e32 v103, 4, v1
	v_lshl_add_u64 v[106:107], v[10:11], 0, s[6:7]
	v_cndmask_b32_e32 v42, v166, v42, vcc
	v_lshlrev_b32_e32 v140, 2, v42
	v_xor_b32_e32 v42, 8, v166
	v_cmp_lt_i32_e32 vcc, v42, v43
	v_and_b32_e32 v10, 0xf0, v103
	v_add_u32_e32 v22, s3, v10
	v_cndmask_b32_e32 v42, v166, v42, vcc
	v_lshlrev_b32_e32 v141, 2, v42
	v_xor_b32_e32 v42, 16, v166
	ds_read_b128 v[10:13], v22
	ds_read_b128 v[14:17], v22 offset:256
	ds_read_b128 v[18:21], v22 offset:512
	ds_read_b128 v[22:25], v22 offset:768
	v_cmp_lt_i32_e32 vcc, v42, v43
	v_mov_b32_e32 v44, v99
	v_mov_b32_e32 v45, v99
	v_cndmask_b32_e32 v42, v166, v42, vcc
	v_lshlrev_b32_e32 v142, 2, v42
	v_xor_b32_e32 v42, 32, v166
	v_cmp_lt_i32_e32 vcc, v42, v43
	s_add_u32 s31, s8, 0x1000
	v_mov_b32_e32 v43, v99
	v_cndmask_b32_e32 v42, v166, v42, vcc
	v_lshlrev_b32_e32 v143, 2, v42
	v_mov_b32_e32 v42, v99
	v_mov_b32_e32 v111, 0xff800000
	v_mov_b32_e32 v110, 0
	v_lshlrev_b32_e32 v98, 4, v50
	v_mov_b64_e32 v[52:53], v[44:45]
	v_mov_b64_e32 v[60:61], v[44:45]
	v_mov_b64_e32 v[64:65], v[44:45]
	s_addc_u32 s42, s9, 0
	s_mov_b32 s48, 0
	s_mov_b32 s43, 32
	v_cmp_eq_u32_e64 s[6:7], 0, v1
	v_cmp_gt_u32_e64 s[8:9], 16, v1
	v_mov_b64_e32 v[50:51], v[42:43]
	v_mov_b64_e32 v[58:59], v[42:43]
	v_mov_b64_e32 v[62:63], v[42:43]
	v_mov_b32_e32 v114, v110
	v_mov_b32_e32 v115, v111
	v_mov_b32_e32 v116, v110
	v_mov_b32_e32 v117, v111
	v_mov_b32_e32 v112, v110
	v_mov_b32_e32 v113, v111
	s_branch .LBB0_5341

.LBB0_5341:
	s_lshr_b32 s10, s48, 2
	s_cmp_lt_u32 s48, 4
	s_cselect_b64 vcc, -1, 0
	s_cmp_eq_u32 s10, 2
	s_cselect_b32 s12, s31, s29
	s_cselect_b32 s13, s42, s30
	s_cmp_eq_u32 s10, 1
	s_cselect_b64 s[10:11], -1, 0
	v_cndmask_b32_e64 v66, v106, v108, s[10:11]
	v_cndmask_b32_e64 v67, v107, v109, s[10:11]
	s_and_b64 s[10:11], s[10:11], exec
	s_cselect_b32 s14, s27, s28
	s_and_b64 s[10:11], vcc, exec
	s_cselect_b32 s14, s26, s14
	s_sub_i32 s10, s43, 32
	s_and_b32 s15, s10, 32
	s_or_b32 s10, s15, s14
	v_add_u32_e32 v80, s10, v100
	v_add_u32_e32 v144, 16, v80
	v_cndmask_b32_e32 v78, v66, v104, vcc
	v_subrev_u32_e32 v66, s14, v144
	v_cndmask_b32_e32 v79, v67, v105, vcc
	v_ashrrev_i32_e32 v67, 31, v66
	v_lshlrev_b64 v[66:67], 10, v[66:67]
	v_lshl_add_u64 v[66:67], v[78:79], 0, v[66:67]
	v_mov_b32_e32 v82, s13
	v_cmp_gt_i32_e64 s[10:11], s44, v144
	v_mov_b32_e32 v83, s12
	v_add_u32_e32 v147, 20, v80
	v_cndmask_b32_e64 v67, v82, v67, s[10:11]
	v_cndmask_b32_e64 v66, v83, v66, s[10:11]
	v_lshl_add_u64 v[66:67], v[66:67], 0, v[98:99]
	v_add_u32_e32 v146, 24, v80
	v_add_u32_e32 v145, 28, v80
	global_load_dwordx4 v[94:97], v[66:67], off nt
	global_load_dwordx4 v[74:77], v[66:67], off offset:512 nt
	v_subrev_u32_e32 v66, s14, v147
	v_subrev_u32_e32 v70, s14, v146
	v_subrev_u32_e32 v80, s14, v145
	v_ashrrev_i32_e32 v67, 31, v66
	v_ashrrev_i32_e32 v71, 31, v70
	v_ashrrev_i32_e32 v81, 31, v80
	v_lshlrev_b64 v[66:67], 10, v[66:67]
	v_lshlrev_b64 v[70:71], 10, v[70:71]
	v_lshlrev_b64 v[80:81], 10, v[80:81]
	v_lshl_add_u64 v[66:67], v[78:79], 0, v[66:67]
	v_lshl_add_u64 v[70:71], v[78:79], 0, v[70:71]
	v_lshl_add_u64 v[78:79], v[78:79], 0, v[80:81]
	s_waitcnt vmcnt(0) lgkmcnt(0)
	v_mul_f32_e32 v80, v11, v3
	v_fmac_f32_e32 v80, v10, v2
	v_fmac_f32_e32 v80, v12, v4
	v_fmac_f32_e32 v80, v13, v5
	ds_bpermute_b32 v81, v138, v80
	v_cmp_gt_i32_e64 s[10:11], s44, v147
	v_mul_f32_e32 v148, v11, v27
	v_fmac_f32_e32 v148, v10, v26
	v_cndmask_b32_e64 v67, v82, v67, s[10:11]
	s_waitcnt lgkmcnt(0)
	v_add_f32_e32 v80, v80, v81
	v_cndmask_b32_e64 v66, v83, v66, s[10:11]
	v_cmp_gt_i32_e64 s[10:11], s44, v146
	ds_bpermute_b32 v81, v139, v80
	v_mul_f32_e32 v125, v23, v3
	v_cndmask_b32_e64 v71, v82, v71, s[10:11]
	v_cndmask_b32_e64 v70, v83, v70, s[10:11]
	v_cmp_gt_i32_e64 s[10:11], s44, v145
	s_waitcnt lgkmcnt(0)
	v_add_f32_e32 v80, v80, v81
	ds_bpermute_b32 v81, v140, v80
	v_cndmask_b32_e64 v79, v82, v79, s[10:11]
	v_mul_f32_e32 v82, v15, v3
	v_fmac_f32_e32 v82, v14, v2
	v_fmac_f32_e32 v82, v16, v4
	v_fmac_f32_e32 v82, v17, v5
	v_cndmask_b32_e64 v78, v83, v78, s[10:11]
	ds_bpermute_b32 v83, v138, v82
	s_and_b32 s10, s48, 12
	s_waitcnt lgkmcnt(1)
	v_add_f32_e32 v118, v80, v81
	s_cmp_eq_u32 s10, 4
	ds_bpermute_b32 v119, v141, v118
	s_waitcnt lgkmcnt(1)
	v_add_f32_e32 v120, v82, v83
	ds_bpermute_b32 v121, v139, v120
	s_cselect_b32 s12, s27, s28
	s_and_b64 s[10:11], vcc, exec
	s_cselect_b32 s10, s26, s12
	s_or_b32 s10, s10, s15
	v_add_u32_e32 v156, s10, v100
	v_sub_u32_e32 v84, 0x800, v156
	s_waitcnt lgkmcnt(1)
	v_add_f32_e32 v118, v118, v119
	s_waitcnt lgkmcnt(0)
	v_add_f32_e32 v119, v120, v121
	v_cvt_f32_u32_e32 v124, v84
	ds_bpermute_b32 v120, v140, v119
	v_cmp_gt_i32_e32 vcc, s2, v156
	v_fmac_f32_e32 v125, v22, v2
	v_fma_f32 v118, -v127, v124, v118
	v_cndmask_b32_e32 v169, v135, v118, vcc
	s_waitcnt lgkmcnt(0)
	v_add_f32_e32 v120, v119, v120
	v_pk_mul_f32 v[118:119], v[12:13], v[28:29]
	v_fmac_f32_e32 v125, v24, v4
	v_add_f32_e32 v118, v118, v148
	v_add_f32_e32 v118, v119, v118
	ds_bpermute_b32 v119, v138, v118
	v_fmac_f32_e32 v125, v25, v5
	ds_bpermute_b32 v148, v138, v125
	v_mul_f32_e32 v150, v15, v27
	v_fmac_f32_e32 v150, v14, v26
	s_waitcnt lgkmcnt(1)
	v_add_f32_e32 v118, v118, v119
	ds_bpermute_b32 v119, v139, v118
	v_fmac_f32_e32 v150, v16, v28
	s_waitcnt lgkmcnt(1)
	v_add_f32_e32 v125, v125, v148
	v_fmac_f32_e32 v150, v17, v29
	ds_bpermute_b32 v148, v139, v125
	s_waitcnt lgkmcnt(1)
	v_add_f32_e32 v118, v118, v119
	ds_bpermute_b32 v119, v140, v118
	ds_bpermute_b32 v151, v138, v150
	s_movk_i32 s10, 0x7fd
	s_waitcnt lgkmcnt(2)
	v_add_f32_e32 v148, v125, v148
	v_sub_u32_e32 v125, 0x7fc, v156
	s_waitcnt lgkmcnt(1)
	v_add_f32_e32 v118, v118, v119
	ds_bpermute_b32 v119, v141, v118
	v_cvt_f32_u32_e32 v125, v125
	v_cmp_gt_i32_e64 s[10:11], s10, v156
	v_mul_f32_e32 v154, v11, v35
	v_fmac_f32_e32 v154, v10, v34
	s_waitcnt lgkmcnt(0)
	v_add_f32_e32 v118, v118, v119
	v_add_f32_e32 v119, v150, v151
	ds_bpermute_b32 v150, v139, v119
	v_mul_f32_e32 v151, v19, v27
	v_fma_f32 v118, -v127, v125, v118
	v_fmac_f32_e32 v151, v18, v26
	v_fmac_f32_e32 v151, v20, v28
	v_cndmask_b32_e64 v172, v135, v118, s[10:11]
	s_waitcnt lgkmcnt(0)
	v_add_f32_e32 v118, v119, v150
	v_fmac_f32_e32 v151, v21, v29
	ds_bpermute_b32 v119, v140, v118
	ds_bpermute_b32 v152, v138, v151
	v_lshl_add_u64 v[66:67], v[66:67], 0, v[98:99]
	v_lshl_add_u64 v[70:71], v[70:71], 0, v[98:99]
	v_lshl_add_u64 v[78:79], v[78:79], 0, v[98:99]
	s_waitcnt lgkmcnt(1)
	v_add_f32_e32 v164, v118, v119
	v_pk_mul_f32 v[118:119], v[12:13], v[36:37]
	s_waitcnt lgkmcnt(0)
	v_add_f32_e32 v150, v151, v152
	v_mul_f32_e32 v152, v23, v27
	v_add_f32_e32 v118, v118, v154
	v_fmac_f32_e32 v152, v22, v26
	v_add_f32_e32 v118, v119, v118
	v_fmac_f32_e32 v152, v24, v28
	ds_bpermute_b32 v119, v138, v118
	v_fmac_f32_e32 v152, v25, v29
	ds_bpermute_b32 v153, v138, v152
	ds_bpermute_b32 v151, v139, v150
	global_load_dwordx4 v[90:93], v[66:67], off nt
	s_nop 0
	global_load_dwordx4 v[66:69], v[66:67], off offset:512 nt
	s_waitcnt lgkmcnt(0)
	v_add_f32_e32 v118, v118, v119
	ds_bpermute_b32 v119, v139, v118
	v_add_f32_e32 v152, v152, v153
	ds_bpermute_b32 v153, v139, v152
	global_load_dwordx4 v[86:89], v[70:71], off nt
	s_nop 0
	global_load_dwordx4 v[70:73], v[70:71], off offset:512 nt
	s_nop 0
	global_load_dwordx4 v[82:85], v[78:79], off nt
	s_nop 0
	global_load_dwordx4 v[78:81], v[78:79], off offset:512 nt
	v_mul_f32_e32 v154, v15, v35
	s_waitcnt lgkmcnt(0)
	v_add_f32_e32 v118, v118, v119
	v_fmac_f32_e32 v154, v14, v34
	ds_bpermute_b32 v119, v140, v118
	v_fmac_f32_e32 v154, v16, v36
	v_add_f32_e32 v150, v150, v151
	v_add_f32_e32 v152, v152, v153
	v_fmac_f32_e32 v154, v17, v37
	ds_bpermute_b32 v151, v140, v150
	ds_bpermute_b32 v153, v140, v152
	ds_bpermute_b32 v155, v138, v154
	s_waitcnt lgkmcnt(0)
	v_add_f32_e32 v118, v118, v119
	ds_bpermute_b32 v119, v141, v118
	v_add_f32_e32 v158, v150, v151
	v_add_f32_e32 v150, v152, v153
	v_sub_u32_e32 v152, 0x7f8, v156
	v_add_f32_e32 v154, v154, v155
	v_cvt_f32_u32_e32 v152, v152
	ds_bpermute_b32 v155, v139, v154
	v_or_b32_e32 v153, 8, v156
	s_waitcnt lgkmcnt(0)
	v_add_f32_e32 v118, v118, v119
	v_fma_f32 v118, -v127, v152, v118
	v_cmp_gt_i32_e64 s[12:13], s2, v153
	v_mul_f32_e32 v153, v19, v35
	v_fmac_f32_e32 v153, v18, v34
	v_cndmask_b32_e64 v173, v135, v118, s[12:13]
	v_add_f32_e32 v118, v154, v155
	v_mul_f32_e32 v155, v23, v35
	v_fmac_f32_e32 v155, v22, v34
	v_fmac_f32_e32 v153, v20, v36
	v_fmac_f32_e32 v155, v24, v36
	v_fmac_f32_e32 v153, v21, v37
	v_fmac_f32_e32 v155, v25, v37
	ds_bpermute_b32 v154, v138, v153
	ds_bpermute_b32 v160, v138, v155
	ds_bpermute_b32 v119, v140, v118
	s_movk_i32 s14, 0x7f5
	v_cmp_gt_i32_e64 s[14:15], s14, v156
	s_waitcnt lgkmcnt(0)
	v_add_f32_e32 v153, v153, v154
	v_add_f32_e32 v160, v155, v160
	v_pk_mul_f32 v[154:155], v[10:11], v[46:47]
	v_add_f32_e32 v167, v118, v119
	v_pk_mul_f32 v[118:119], v[12:13], v[48:49]
	v_add_f32_e32 v154, v154, v155
	v_add_f32_e32 v118, v118, v154
	ds_bpermute_b32 v161, v139, v153
	ds_bpermute_b32 v162, v139, v160
	v_add_f32_e32 v118, v119, v118
	ds_bpermute_b32 v119, v138, v118
	v_mul_f32_e32 v122, v19, v3
	s_waitcnt lgkmcnt(0)
	v_add_f32_e32 v153, v153, v161
	v_add_f32_e32 v155, v160, v162
	ds_bpermute_b32 v154, v140, v153
	ds_bpermute_b32 v162, v140, v155
	v_add_f32_e32 v118, v118, v119
	ds_bpermute_b32 v119, v139, v118
	v_fmac_f32_e32 v122, v18, v2
	s_waitcnt lgkmcnt(0)
	v_add_f32_e32 v160, v153, v154
	v_add_f32_e32 v153, v155, v162
	v_mul_f32_e32 v162, v15, v47
	v_add_f32_e32 v118, v118, v119
	v_fmac_f32_e32 v162, v14, v46
	ds_bpermute_b32 v119, v140, v118
	v_fmac_f32_e32 v162, v16, v48
	v_fmac_f32_e32 v162, v17, v49
	ds_bpermute_b32 v163, v138, v162
	v_sub_u32_e32 v155, 0x7f4, v156
	s_waitcnt lgkmcnt(0)
	v_add_f32_e32 v118, v118, v119
	ds_bpermute_b32 v119, v141, v118
	v_cvt_f32_u32_e32 v155, v155
	v_add_f32_e32 v162, v162, v163
	ds_bpermute_b32 v163, v139, v162
	v_mul_f32_e32 v156, v19, v47
	s_waitcnt lgkmcnt(0)
	v_add_f32_e32 v118, v118, v119
	v_fma_f32 v118, -v127, v155, v118
	v_cndmask_b32_e64 v174, v135, v118, s[14:15]
	v_add_f32_e32 v118, v162, v163
	v_mul_f32_e32 v163, v23, v47
	v_fmac_f32_e32 v156, v18, v46
	v_fmac_f32_e32 v163, v22, v46
	v_fmac_f32_e32 v122, v20, v4
	v_fmac_f32_e32 v156, v20, v48
	v_fmac_f32_e32 v163, v24, v48
	v_fmac_f32_e32 v122, v21, v5
	v_fmac_f32_e32 v156, v21, v49
	v_fmac_f32_e32 v163, v25, v49
	ds_bpermute_b32 v123, v138, v122
	ds_bpermute_b32 v119, v140, v118
	ds_bpermute_b32 v162, v138, v156
	ds_bpermute_b32 v171, v138, v163
	v_max3_f32 v157, v169, s33, v172
	s_waitcnt lgkmcnt(0)
	v_add_f32_e32 v122, v122, v123
	v_add_f32_e32 v170, v118, v119
	v_add_f32_e32 v118, v156, v162
	v_add_f32_e32 v156, v163, v171
	ds_bpermute_b32 v123, v139, v122
	ds_bpermute_b32 v119, v139, v118
	ds_bpermute_b32 v162, v139, v156
	v_max3_f32 v157, v157, v173, v174
	ds_bpermute_b32 v163, v142, v157
	s_waitcnt lgkmcnt(0)
	v_add_f32_e32 v122, v122, v123
	v_add_f32_e32 v118, v118, v119
	v_add_f32_e32 v156, v156, v162
	ds_bpermute_b32 v123, v140, v122
	ds_bpermute_b32 v149, v140, v148
	ds_bpermute_b32 v119, v140, v118
	ds_bpermute_b32 v175, v140, v156
	v_max_f32_e32 v162, v163, v163
	v_max_f32_e32 v176, v157, v162
	ds_bpermute_b32 v177, v143, v176
	s_waitcnt lgkmcnt(0)
	v_add_f32_e32 v122, v122, v123
	v_add_f32_e32 v148, v148, v149
	v_add_f32_e32 v162, v118, v119
	v_add_f32_e32 v156, v156, v175
	ds_bpermute_b32 v121, v141, v120
	ds_bpermute_b32 v123, v141, v122
	ds_bpermute_b32 v149, v141, v148
	ds_bpermute_b32 v165, v141, v164
	ds_bpermute_b32 v159, v141, v158
	ds_bpermute_b32 v151, v141, v150
	ds_bpermute_b32 v168, v141, v167
	ds_bpermute_b32 v161, v141, v160
	ds_bpermute_b32 v154, v141, v153
	ds_bpermute_b32 v171, v141, v170
	ds_bpermute_b32 v163, v141, v162
	ds_bpermute_b32 v157, v141, v156
	v_max_f32_e32 v118, v177, v177
	v_max_f32_e32 v175, v176, v118
	v_cmp_neq_f32_e64 s[16:17], s33, v175
	v_mov_b64_e32 v[118:119], v[112:113]
	s_and_saveexec_b64 s[22:23], s[16:17]
	s_cbranch_execz .LBB0_5343
	v_max_f32_e32 v118, v175, v175
	v_max_f32_e32 v119, v113, v113
	v_max_f32_e32 v119, v119, v118
	v_sub_f32_e32 v118, v169, v119
	v_mul_f32_e32 v118, 0x3fb8aa3b, v118
	v_exp_f32_e32 v118, v118
	v_sub_f32_e32 v113, v113, v119
	v_mul_f32_e32 v113, 0x3fb8aa3b, v113
	v_add_f32_e32 v169, 0, v118
	v_pk_fma_f32 v[176:177], v[8:9], v[118:119], 0 op_sel_hi:[1,0,0]
	v_pk_fma_f32 v[178:179], v[6:7], v[118:119], 0 op_sel_hi:[1,0,0]
	v_sub_f32_e32 v118, v172, v119
	v_mul_f32_e32 v118, 0x3fb8aa3b, v118
	v_exp_f32_e32 v118, v118
	s_nop 0
	v_add_f32_e32 v169, v118, v169
	v_pk_fma_f32 v[176:177], v[32:33], v[118:119], v[176:177] op_sel_hi:[1,0,1]
	v_pk_fma_f32 v[178:179], v[30:31], v[118:119], v[178:179] op_sel_hi:[1,0,1]
	v_sub_f32_e32 v118, v173, v119
	v_mul_f32_e32 v118, 0x3fb8aa3b, v118
	v_exp_f32_e32 v118, v118
	s_nop 0
	v_add_f32_e32 v169, v118, v169
	v_pk_fma_f32 v[172:173], v[38:39], v[118:119], v[178:179] op_sel_hi:[1,0,1]
	v_pk_fma_f32 v[176:177], v[40:41], v[118:119], v[176:177] op_sel_hi:[1,0,1]
	v_sub_f32_e32 v118, v174, v119
	v_mul_f32_e32 v118, 0x3fb8aa3b, v118
	v_exp_f32_e32 v118, v118
	s_nop 0
	v_add_f32_e32 v169, v118, v169
	v_pk_fma_f32 v[174:175], v[56:57], v[118:119], v[176:177] op_sel_hi:[1,0,1]
	v_exp_f32_e32 v176, v113
	ds_bpermute_b32 v113, v142, v169
	v_pk_fma_f32 v[172:173], v[54:55], v[118:119], v[172:173] op_sel_hi:[1,0,1]
	ds_bpermute_b32 v178, v142, v174
	ds_bpermute_b32 v179, v142, v175
	s_waitcnt lgkmcnt(0)
	v_add_f32_e32 v113, v169, v113
	ds_bpermute_b32 v118, v143, v113
	v_pk_add_f32 v[174:175], v[174:175], v[178:179]
	ds_bpermute_b32 v178, v143, v174
	ds_bpermute_b32 v179, v143, v175
	s_waitcnt lgkmcnt(0)
	v_add_f32_e32 v118, v113, v118
	v_fmac_f32_e32 v118, v112, v176
	ds_bpermute_b32 v112, v142, v172
	ds_bpermute_b32 v113, v142, v173
	s_waitcnt lgkmcnt(0)
	v_pk_add_f32 v[112:113], v[172:173], v[112:113]
	ds_bpermute_b32 v172, v143, v112
	ds_bpermute_b32 v173, v143, v113
	s_waitcnt lgkmcnt(0)
	v_pk_add_f32 v[112:113], v[112:113], v[172:173]
	v_pk_add_f32 v[172:173], v[174:175], v[178:179]
	v_pk_fma_f32 v[62:63], v[62:63], v[176:177], v[112:113] op_sel_hi:[1,0,1]
	v_pk_fma_f32 v[64:65], v[64:65], v[176:177], v[172:173] op_sel_hi:[1,0,1]
	v_mov_b32_e32 v112, v118
	v_mov_b32_e32 v113, v119

.LBB0_5349:
	s_or_b64 exec, exec, s[10:11]
	s_add_i32 s49, s48, 2
	s_cmp_gt_u32 s48, 9
	s_cselect_b64 s[22:23], -1, 0
	s_and_b64 vcc, exec, s[22:23]
	s_cbranch_vccnz .LBB0_5351
	s_lshr_b32 s10, s49, 2
	s_cmp_eq_u32 s10, 2
	s_cselect_b32 s12, s31, s29
	s_cselect_b32 s13, s42, s30
	s_cmp_eq_u32 s10, 1
	s_cselect_b64 vcc, -1, 0
	s_and_b64 s[10:11], vcc, exec
	s_cselect_b32 s14, s27, s28
	s_cmp_eq_u32 s48, 0
	v_cndmask_b32_e32 v2, v106, v108, vcc
	v_cndmask_b32_e32 v3, v107, v109, vcc
	s_cselect_b64 vcc, -1, 0
	s_and_b64 s[10:11], vcc, exec
	s_cselect_b32 s10, s26, s14
	s_and_b32 s11, s43, 32
	s_or_b32 s11, s10, s11
	v_add_u32_e32 v54, s11, v100
	v_subrev_u32_e32 v48, s10, v54
	v_ashrrev_i32_e32 v49, 31, v48
	v_add_u32_e32 v26, 4, v48
	v_or_b32_e32 v36, 8, v54
	v_cndmask_b32_e32 v47, v3, v105, vcc
	v_cndmask_b32_e32 v46, v2, v104, vcc
	v_lshlrev_b64 v[2:3], 10, v[48:49]
	v_ashrrev_i32_e32 v27, 31, v26
	v_subrev_u32_e32 v34, s10, v36
	v_lshl_add_u64 v[2:3], v[46:47], 0, v[2:3]
	v_mov_b32_e32 v55, s13
	v_cmp_gt_i32_e32 vcc, s44, v54
	v_mov_b32_e32 v56, s12
	v_lshlrev_b64 v[26:27], 10, v[26:27]
	s_movk_i32 s11, 0x7fc
	v_ashrrev_i32_e32 v35, 31, v34
	v_add_u32_e32 v48, 12, v48
	v_cndmask_b32_e32 v3, v55, v3, vcc
	v_cndmask_b32_e32 v2, v56, v2, vcc
	v_lshl_add_u64 v[26:27], v[46:47], 0, v[26:27]
	v_cmp_gt_i32_e32 vcc, s11, v54
	v_lshlrev_b64 v[34:35], 10, v[34:35]
	v_ashrrev_i32_e32 v49, 31, v48
	v_cndmask_b32_e32 v27, v55, v27, vcc
	v_cndmask_b32_e32 v26, v56, v26, vcc
	v_lshl_add_u64 v[34:35], v[46:47], 0, v[34:35]
	v_cmp_gt_i32_e32 vcc, s44, v36
	v_lshlrev_b64 v[48:49], 10, v[48:49]
	s_movk_i32 s10, 0x7f4
	v_cndmask_b32_e32 v35, v55, v35, vcc
	v_cndmask_b32_e32 v34, v56, v34, vcc
	v_lshl_add_u64 v[46:47], v[46:47], 0, v[48:49]
	v_cmp_gt_i32_e32 vcc, s10, v54
	v_lshl_add_u64 v[6:7], v[2:3], 0, v[98:99]
	v_lshl_add_u64 v[30:31], v[26:27], 0, v[98:99]
	v_cndmask_b32_e32 v47, v55, v47, vcc
	v_cndmask_b32_e32 v46, v56, v46, vcc
	v_lshl_add_u64 v[38:39], v[34:35], 0, v[98:99]
	v_lshl_add_u64 v[54:55], v[46:47], 0, v[98:99]
	global_load_dwordx4 v[2:5], v[6:7], off nt
	s_nop 0
	global_load_dwordx4 v[6:9], v[6:7], off offset:512 nt
	s_nop 0
	global_load_dwordx4 v[26:29], v[30:31], off nt
	s_nop 0
	global_load_dwordx4 v[30:33], v[30:31], off offset:512 nt
	s_nop 0
	global_load_dwordx4 v[34:37], v[38:39], off nt
	s_nop 0
	global_load_dwordx4 v[38:41], v[38:39], off offset:512 nt
	s_nop 0
	global_load_dwordx4 v[46:49], v[54:55], off nt
	s_nop 0
	global_load_dwordx4 v[54:57], v[54:55], off offset:512 nt

.LBB0_5382:
	s_or_b64 exec, exec, s[6:7]
	v_mov_b32_e32 v2, v139
	s_add_u32 s6, s68, s84
	v_ashrrev_i32_e32 v3, 5, v2
	v_lshlrev_b32_e32 v6, 3, v3
	v_ashrrev_i32_e32 v7, 31, v6
	s_addc_u32 s7, s69, 0
	v_lshl_add_u64 v[6:7], v[6:7], 1, v[94:95]
	s_add_u32 s6, s6, s49
	global_load_dwordx4 v[66:69], v[6:7], off
	global_load_dwordx4 v[70:73], v[6:7], off offset:32
	global_load_dwordx4 v[74:77], v[6:7], off offset:64
	global_load_dwordx4 v[78:81], v[6:7], off offset:96
	v_min_i32_e32 v6, 0x1ff, v2
	s_addc_u32 s7, s7, 0
	v_ashrrev_i32_e32 v7, 31, v6
	s_add_u32 s6, s6, 0x28840000
	v_lshlrev_b64 v[6:7], 8, v[6:7]
	s_addc_u32 s7, s7, 0
	v_lshl_add_u64 v[6:7], s[22:23], 0, v[6:7]
	s_lshl_b32 s8, s28, 4
	v_lshlrev_b32_e32 v4, 3, v2
	v_lshl_add_u64 v[8:9], s[70:71], 1, v[6:7]
	s_and_b32 s48, s8, 48
	v_ashrrev_i32_e32 v6, 2, v2
	v_and_b32_e32 v5, 24, v4
	v_add_u32_e32 v4, s48, v6
	v_min_i32_e32 v10, 0x1ff, v4
	v_ashrrev_i32_e32 v11, 31, v10
	v_lshlrev_b64 v[10:11], 8, v[10:11]
	s_and_b32 s72, s70, 0xffffffe0
	v_lshl_add_u64 v[10:11], s[6:7], 0, v[10:11]
	s_ashr_i32 s73, s72, 31
	v_lshl_add_u64 v[10:11], s[72:73], 1, v[10:11]
	v_lshlrev_b32_e32 v98, 1, v5
	s_waitcnt lgkmcnt(0)
	s_barrier
	v_lshl_add_u64 v[10:11], v[10:11], 0, v[98:99]
	global_load_dwordx4 v[82:85], v[8:9], off
	global_load_dwordx4 v[86:89], v[10:11], off
	v_lshl_add_u32 v124, v2, 4, s85
	s_andn2_b64 vcc, exec, s[24:25]
	s_waitcnt vmcnt(0) lgkmcnt(0)
	ds_write_b128 v124, v[82:85]
	ds_write_b128 v124, v[86:89] offset:16384
	s_waitcnt lgkmcnt(0)
	s_barrier
	s_cbranch_vccnz .LBB0_5384
	v_min_i32_e32 v8, 0x1bf, v2
	v_ashrrev_i32_e32 v9, 31, v8
	v_add3_u32 v6, v6, s48, 64
	v_lshlrev_b64 v[8:9], 8, v[8:9]
	v_min_i32_e32 v6, 0x1ff, v6
	v_lshl_add_u64 v[8:9], s[22:23], 0, v[8:9]
	v_ashrrev_i32_e32 v7, 31, v6
	v_lshl_add_u64 v[8:9], s[70:71], 1, v[8:9]
	v_lshlrev_b64 v[6:7], 8, v[6:7]
	v_add_co_u32_e32 v8, vcc, 0x4000, v8
	v_lshl_add_u64 v[6:7], s[6:7], 0, v[6:7]
	s_nop 0
	v_addc_co_u32_e32 v9, vcc, 0, v9, vcc
	v_lshl_add_u64 v[6:7], s[72:73], 1, v[6:7]
	v_lshl_add_u64 v[6:7], v[6:7], 0, v[98:99]
	global_load_dwordx4 v[82:85], v[8:9], off
	global_load_dwordx4 v[86:89], v[6:7], off

.LBB0_5386:
	s_and_b32 s43, s31, 0x2000
	v_add_u32_e32 v112, s43, v142
	ds_read_b128 v[34:37], v112
	ds_read_b128 v[146:149], v112 offset:2048
	ds_read_b128 v[230:233], v112 offset:512
	ds_read_b128 v[234:237], v112 offset:2560
	ds_read_b128 v[238:241], v112 offset:4096
	ds_read_b128 v[242:245], v112 offset:4608
	ds_read_b128 v[246:249], v112 offset:6144
	ds_read_b128 v[250:253], v112 offset:6656
	s_waitcnt lgkmcnt(6)
	v_mfma_f32_32x32x16_bf16 v[50:65], v[34:37], v[66:69], 0
	v_mfma_f32_32x32x16_bf16 v[50:65], v[146:149], v[70:73], v[50:65]
	s_waitcnt lgkmcnt(4)
	v_mfma_f32_32x32x16_bf16 v[34:49], v[230:233], v[66:69], 0
	v_mfma_f32_32x32x16_bf16 v[34:49], v[234:237], v[70:73], v[34:49]
	s_waitcnt lgkmcnt(3)
	v_mfma_f32_32x32x16_bf16 v[50:65], v[238:241], v[74:77], v[50:65]
	s_waitcnt lgkmcnt(2)
	v_mfma_f32_32x32x16_bf16 v[34:49], v[242:245], v[74:77], v[34:49]
	s_waitcnt lgkmcnt(1)
	v_mfma_f32_32x32x16_bf16 v[50:65], v[246:249], v[78:81], v[50:65]
	s_waitcnt lgkmcnt(0)
	v_mfma_f32_32x32x16_bf16 v[34:49], v[250:253], v[78:81], v[34:49]
	v_cvt_f32_i32_e32 v112, v121
	v_cmp_lt_i32_e64 s[22:23], 62, v1
	s_cmp_eq_u64 s[22:23], exec
	v_fma_f32 v154, v90, v112, v141
	v_add_f32_e32 v146, v120, v154
	v_add_f32_e32 v148, v105, v154
	v_add_f32_e32 v147, v92, v146
	v_add_f32_e32 v149, v92, v148
	s_nop 0
	v_pk_add_f32 v[112:113], v[146:147], v[50:51]
	v_pk_add_f32 v[50:51], v[102:103], v[146:147] op_sel_hi:[1,0]
	v_add_f32_e32 v152, v107, v154
	v_pk_add_f32 v[50:51], v[50:51], v[52:53]
	v_pk_add_f32 v[52:53], v[148:149], v[54:55]
	v_pk_add_f32 v[54:55], v[102:103], v[148:149] op_sel_hi:[1,0]
	v_add_f32_e32 v149, v119, v154
	v_pk_add_f32 v[54:55], v[54:55], v[56:57]
	v_add_f32_e32 v56, v120, v149
	v_add_f32_e32 v57, v92, v56
	v_pk_add_f32 v[34:35], v[56:57], v[34:35]
	v_add_f32_e32 v57, v102, v56
	v_add_f32_e32 v146, v57, v36
	v_mov_b32_e32 v57, v149
	v_pk_add_f32 v[150:151], v[104:105], v[56:57]
	v_mov_b32_e32 v36, v37
	v_mov_b32_e32 v37, v38
	v_pk_add_f32 v[56:57], v[92:93], v[150:151] op_sel:[0,1]
	v_mov_b32_e32 v38, v39
	v_mov_b32_e32 v39, v40
	v_add_f32_e32 v153, v92, v152
	v_mov_b32_e32 v148, v151
	v_pk_add_f32 v[36:37], v[150:151], v[36:37]
	v_pk_add_f32 v[38:39], v[56:57], v[38:39]
	v_pk_add_f32 v[56:57], v[152:153], v[58:59]
	v_pk_add_f32 v[58:59], v[102:103], v[152:153] op_sel_hi:[1,0]
	v_pk_add_f32 v[150:151], v[106:107], v[148:149]
	v_add_f32_e32 v152, v109, v154
	v_pk_add_f32 v[58:59], v[58:59], v[60:61]
	v_mov_b32_e32 v40, v41
	v_mov_b32_e32 v41, v42
	v_pk_add_f32 v[60:61], v[92:93], v[150:151] op_sel:[0,1]
	v_mov_b32_e32 v42, v43
	v_mov_b32_e32 v43, v44
	v_add_f32_e32 v153, v92, v152
	v_pk_add_f32 v[42:43], v[60:61], v[42:43]
	v_pk_add_f32 v[60:61], v[152:153], v[62:63]
	v_pk_add_f32 v[62:63], v[102:103], v[152:153] op_sel_hi:[1,0]
	v_mov_b32_e32 v148, v151
	v_pk_add_f32 v[62:63], v[62:63], v[64:65]
	v_pk_add_f32 v[64:65], v[108:109], v[148:149]
	v_mov_b32_e32 v44, v45
	v_mov_b32_e32 v45, v46
	v_pk_add_f32 v[148:149], v[92:93], v[64:65] op_sel:[0,1]
	v_mov_b32_e32 v46, v47
	v_mov_b32_e32 v47, v48
	v_add_f32_e32 v48, v104, v65
	v_pk_add_f32 v[40:41], v[150:151], v[40:41]
	v_pk_add_f32 v[44:45], v[64:65], v[44:45]
	v_pk_add_f32 v[46:47], v[148:149], v[46:47]
	v_add_f32_e32 v64, v48, v49
	s_cbranch_scc1 .LBB0_5388
	v_add_u32_e32 v48, v145, v1
	v_cmp_gt_i32_e64 s[22:23], 0, v48
	s_or_b64 s[22:23], s[6:7], s[22:23]
	v_cmp_gt_i32_e64 s[24:25], 40, v48
	v_cndmask_b32_e64 v112, v112, v132, s[22:23]
	v_cmp_gt_i32_e64 s[22:23], 32, v48
	s_or_b64 s[22:23], s[12:13], s[22:23]
	s_nop 0
	v_cndmask_b32_e64 v34, v34, v132, s[22:23]
	v_cmp_gt_i32_e64 s[22:23], 1, v48
	s_or_b64 s[22:23], s[6:7], s[22:23]
	s_nop 0
	v_cndmask_b32_e64 v113, v113, v132, s[22:23]
	v_cmp_gt_i32_e64 s[22:23], 33, v48
	s_or_b64 s[22:23], s[12:13], s[22:23]
	s_nop 0
	v_cndmask_b32_e64 v35, v35, v132, s[22:23]
	v_cmp_gt_i32_e64 s[22:23], 2, v48
	s_or_b64 s[22:23], s[6:7], s[22:23]
	s_nop 0
	v_cndmask_b32_e64 v50, v50, v132, s[22:23]
	v_cmp_gt_i32_e64 s[22:23], 34, v48
	s_or_b64 s[22:23], s[12:13], s[22:23]
	s_nop 0
	v_cndmask_b32_e64 v146, v146, v132, s[22:23]
	v_cmp_gt_i32_e64 s[22:23], 3, v48
	s_or_b64 s[22:23], s[6:7], s[22:23]
	s_nop 0
	v_cndmask_b32_e64 v51, v51, v132, s[22:23]
	v_cmp_gt_i32_e64 s[22:23], 8, v48
	s_or_b64 s[22:23], s[8:9], s[22:23]
	s_nop 0
	v_cndmask_b32_e64 v52, v52, v132, s[22:23]
	v_cmp_gt_i32_e64 s[22:23], 35, v48
	s_or_b64 s[22:23], s[12:13], s[22:23]
	s_nop 0
	v_cndmask_b32_e64 v36, v36, v132, s[22:23]
	s_or_b64 s[22:23], s[10:11], s[24:25]
	v_cndmask_b32_e64 v37, v37, v132, s[22:23]
	v_cmp_gt_i32_e64 s[22:23], 9, v48
	s_or_b64 s[22:23], s[8:9], s[22:23]
	s_nop 0
	v_cndmask_b32_e64 v53, v53, v132, s[22:23]
	v_cmp_gt_i32_e64 s[22:23], 41, v48
	s_or_b64 s[22:23], s[10:11], s[22:23]
	s_nop 0
	v_cndmask_b32_e64 v38, v38, v132, s[22:23]
	v_cmp_gt_i32_e64 s[22:23], 10, v48
	s_or_b64 s[22:23], s[8:9], s[22:23]
	s_nop 0
	v_cndmask_b32_e64 v54, v54, v132, s[22:23]
	v_cmp_gt_i32_e64 s[22:23], 42, v48
	s_or_b64 s[22:23], s[10:11], s[22:23]
	s_nop 0
	v_cndmask_b32_e64 v39, v39, v132, s[22:23]
	v_cmp_gt_i32_e64 s[22:23], 11, v48
	s_or_b64 s[22:23], s[8:9], s[22:23]
	s_nop 0
	v_cndmask_b32_e64 v55, v55, v132, s[22:23]
	v_cmp_gt_i32_e64 s[22:23], 43, v48
	s_or_b64 s[22:23], s[10:11], s[22:23]
	s_nop 0
	v_cndmask_b32_e64 v40, v40, v132, s[22:23]
	v_cmp_gt_i32_e64 s[22:23], 16, v48
	s_or_b64 s[22:23], s[14:15], s[22:23]
	s_nop 0
	v_cndmask_b32_e64 v56, v56, v132, s[22:23]
	v_cmp_gt_i32_e64 s[22:23], 48, v48
	s_or_b64 s[22:23], s[16:17], s[22:23]
	s_nop 0
	v_cndmask_b32_e64 v41, v41, v132, s[22:23]
	v_cmp_gt_i32_e64 s[22:23], 17, v48
	s_or_b64 s[22:23], s[14:15], s[22:23]
	s_nop 0
	v_cndmask_b32_e64 v57, v57, v132, s[22:23]
	v_cmp_gt_i32_e64 s[22:23], 49, v48
	s_or_b64 s[22:23], s[16:17], s[22:23]
	s_nop 0
	v_cndmask_b32_e64 v42, v42, v132, s[22:23]
	v_cmp_gt_i32_e64 s[22:23], 18, v48
	s_or_b64 s[22:23], s[14:15], s[22:23]
	s_nop 0
	v_cndmask_b32_e64 v58, v58, v132, s[22:23]
	v_cmp_gt_i32_e64 s[22:23], 50, v48
	s_or_b64 s[22:23], s[16:17], s[22:23]
	s_nop 0
	v_cndmask_b32_e64 v43, v43, v132, s[22:23]
	v_cmp_gt_i32_e64 s[22:23], 19, v48
	s_or_b64 s[22:23], s[14:15], s[22:23]
	s_nop 0
	v_cndmask_b32_e64 v59, v59, v132, s[22:23]
	v_cmp_gt_i32_e64 s[22:23], 51, v48
	s_or_b64 s[22:23], s[16:17], s[22:23]
	s_nop 0
	v_cndmask_b32_e64 v44, v44, v132, s[22:23]
	v_cmp_gt_i32_e64 s[22:23], 24, v48
	s_or_b64 s[22:23], s[18:19], s[22:23]
	s_nop 0
	v_cndmask_b32_e64 v60, v60, v132, s[22:23]
	v_cmp_gt_i32_e64 s[22:23], 56, v48
	s_or_b64 s[22:23], s[20:21], s[22:23]
	s_nop 0
	v_cndmask_b32_e64 v45, v45, v132, s[22:23]
	v_cmp_gt_i32_e64 s[22:23], 25, v48
	s_or_b64 s[22:23], s[18:19], s[22:23]
	s_nop 0
	v_cndmask_b32_e64 v61, v61, v132, s[22:23]
	v_cmp_gt_i32_e64 s[22:23], 57, v48
	s_or_b64 s[22:23], s[20:21], s[22:23]
	s_nop 0
	v_cndmask_b32_e64 v46, v46, v132, s[22:23]
	v_cmp_gt_i32_e64 s[22:23], 26, v48
	s_or_b64 s[22:23], s[18:19], s[22:23]
	s_nop 0
	v_cndmask_b32_e64 v62, v62, v132, s[22:23]
	v_cmp_gt_i32_e64 s[22:23], 58, v48
	s_or_b64 s[22:23], s[20:21], s[22:23]
	s_nop 0
	v_cndmask_b32_e64 v47, v47, v132, s[22:23]
	v_cmp_gt_i32_e64 s[22:23], 27, v48
	s_or_b64 s[22:23], s[18:19], s[22:23]
	s_nop 0
	v_cndmask_b32_e64 v63, v63, v132, s[22:23]
	v_cmp_gt_i32_e64 s[22:23], 59, v48
	s_or_b64 s[22:23], s[20:21], s[22:23]
	s_nop 0
	v_cndmask_b32_e64 v64, v64, v132, s[22:23]

.LBB0_5394:
	s_add_i32 s22, s42, 2
	s_cmp_gt_u32 s22, s30
	s_waitcnt lgkmcnt(0)
	s_barrier
	s_cbranch_scc1 .LBB0_5385
	v_min_i32_e32 v34, 0x1ff, v143
	v_ashrrev_i32_e32 v35, 31, v34
	v_min_i32_e32 v36, 0x1ff, v98
	v_lshlrev_b64 v[34:35], 8, v[34:35]
	v_ashrrev_i32_e32 v37, 31, v36
	v_lshl_add_u64 v[34:35], s[26:27], 0, v[34:35]
	v_lshlrev_b64 v[36:37], 8, v[36:37]
	v_lshl_add_u64 v[36:37], v[110:111], 0, v[36:37]
	s_waitcnt vmcnt(0)
	global_load_dwordx4 v[82:85], v[34:35], off
	global_load_dwordx4 v[86:89], v[36:37], off
	s_branch .LBB0_5385

.LBB0_5398:
	s_andn2_b64 vcc, exec, s[20:21]
	s_waitcnt lgkmcnt(0)
	s_barrier
	s_cbranch_vccnz .LBB0_5400
	s_mul_i32 s6, s5, 0x108
	s_add_i32 s10, s3, s6
	s_add_i32 s6, s10, 0x4c40
	v_mov_b32_e32 v2, s6
	s_add_i32 s6, s10, 0x5060
	v_mov_b32_e32 v4, s6
	s_add_i32 s6, s10, 0x5480
	v_mov_b32_e32 v5, s6
	s_add_i32 s6, s10, 0x58a0
	v_mov_b32_e32 v6, s6
	s_add_i32 s6, s10, 0x5cc0
	ds_read2_b32 v[2:3], v2 offset1:1
	ds_read2_b32 v[8:9], v4 offset1:1
	ds_read2_b32 v[10:11], v5 offset1:1
	ds_read2_b32 v[12:13], v6 offset1:1
	v_mov_b32_e32 v4, s6
	s_add_i32 s6, s10, 0x60e0
	v_mov_b32_e32 v5, s6
	s_add_i32 s6, s10, 0x6500
	v_mov_b32_e32 v6, s6
	s_add_i32 s6, s10, 0x6920
	v_mov_b32_e32 v7, s6
	ds_read2_b32 v[14:15], v4 offset1:1
	ds_read2_b32 v[16:17], v5 offset1:1
	ds_read2_b32 v[18:19], v6 offset1:1
	ds_read2_b32 v[20:21], v7 offset1:1
	s_waitcnt lgkmcnt(6)
	v_max3_f32 v4, v2, s33, v8
	s_waitcnt lgkmcnt(4)
	v_max3_f32 v4, v4, v10, v12
	s_waitcnt lgkmcnt(2)
	v_max3_f32 v4, v4, v14, v16
	v_readlane_b32 s12, v228, 22
	s_waitcnt lgkmcnt(0)
	v_max3_f32 v4, v4, v18, v20
	v_sub_f32_e32 v2, v2, v4
	v_mul_f32_e32 v2, 0x3fb8aa3b, v2
	v_exp_f32_e32 v7, v2
	v_sub_f32_e32 v2, v8, v4
	v_mul_f32_e32 v2, 0x3fb8aa3b, v2
	v_exp_f32_e32 v6, v2
	v_mov_b32_e32 v2, v9
	v_sub_f32_e32 v8, v10, v4
	v_sub_f32_e32 v9, v12, v4
	v_mul_f32_e32 v8, 0x3fb8aa3b, v8
	v_mul_f32_e32 v9, 0x3fb8aa3b, v9
	v_exp_f32_e32 v8, v8
	v_exp_f32_e32 v9, v9
	v_mov_b32_e32 v12, v11
	v_sub_f32_e32 v10, v14, v4
	v_sub_f32_e32 v11, v16, v4
	v_mul_f32_e32 v10, 0x3fb8aa3b, v10
	v_mul_f32_e32 v11, 0x3fb8aa3b, v11
	v_pk_mul_f32 v[2:3], v[2:3], v[6:7]
	v_exp_f32_e32 v10, v10
	v_exp_f32_e32 v11, v11
	v_add_f32_e32 v3, 0, v3
	v_add_f32_e32 v22, v2, v3
	v_pk_mul_f32 v[2:3], v[8:9], v[12:13]
	v_mov_b32_e32 v16, v15
	v_add_f32_e32 v2, v2, v22
	s_add_i32 s6, s10, 0x6d40
	s_lshl_b32 s11, s5, 8
	s_add_i32 s5, s5, s12
	v_add_f32_e32 v14, v2, v3
	v_pk_mul_f32 v[2:3], v[10:11], v[16:17]
	v_mov_b32_e32 v16, s6
	s_add_i32 s6, s10, 0x7160
	s_mul_i32 s12, s5, 3
	v_sub_f32_e32 v12, v18, v4
	v_sub_f32_e32 v4, v20, v4
	v_mov_b32_e32 v20, v19
	v_mov_b32_e32 v19, s6
	s_add_i32 s6, s10, 0x7580
	s_ashr_i32 s13, s12, 31
	v_add_u32_e32 v5, s10, v102
	v_mov_b32_e32 v22, s6
	s_add_i32 s6, s10, 0x79a0
	s_add_i32 s7, s10, 0x7dc0
	s_add_i32 s8, s10, 0x81e0
	s_add_i32 s9, s10, 0x8600
	s_add_i32 s10, s10, 0x8a20
	s_add_i32 s11, s3, s11
	s_lshl_b64 s[12:13], s[12:13], 2
	v_add_f32_e32 v2, v14, v2
	s_add_u32 s12, s18, s12
	v_add_f32_e32 v18, v2, v3
	s_addc_u32 s13, s19, s13
	v_mov_b32_e32 v2, s12
	s_movk_i32 s12, 0x1000
	v_mov_b32_e32 v3, s13
	v_add_co_u32_e32 v2, vcc, s12, v2
	v_mul_f32_e32 v4, 0x3fb8aa3b, v4
	s_nop 0
	v_addc_co_u32_e32 v3, vcc, 0, v3, vcc
	v_exp_f32_e32 v13, v4
	global_load_dwordx3 v[2:4], v[2:3], off offset:1024
	v_mul_f32_e32 v12, 0x3fb8aa3b, v12
	v_exp_f32_e32 v12, v12
	v_mov_b32_e32 v24, s6
	v_mov_b32_e32 v28, s8
	v_mov_b32_e32 v29, s9
	v_pk_mul_f32 v[14:15], v[12:13], v[20:21]
	ds_read2_b32 v[16:17], v16 offset1:1
	ds_read2_b32 v[20:21], v19 offset1:1
	ds_read2_b32 v[22:23], v22 offset1:1
	ds_read2_b32 v[24:25], v24 offset1:1
	v_mov_b32_e32 v19, s7
	v_mov_b32_e32 v30, s10
	ds_read2_b32 v[26:27], v19 offset1:1
	ds_read2_b32 v[38:39], v28 offset1:1
	ds_read2_b32 v[40:41], v29 offset1:1
	ds_read2_b32 v[42:43], v30 offset1:1
	v_add_f32_e32 v14, v18, v14
	s_waitcnt lgkmcnt(0)
	v_max3_f32 v18, v16, s33, v20
	v_max3_f32 v18, v18, v22, v24
	v_max3_f32 v18, v18, v26, v38
	v_max3_f32 v28, v18, v40, v42
	v_sub_f32_e32 v16, v16, v28
	v_mul_f32_e32 v16, 0x3fb8aa3b, v16
	v_exp_f32_e32 v19, v16
	v_sub_f32_e32 v16, v20, v28
	v_mul_f32_e32 v16, 0x3fb8aa3b, v16
	v_exp_f32_e32 v18, v16
	v_add_f32_e32 v14, v14, v15
	v_mov_b32_e32 v16, v21
	v_max_f32_e32 v44, 0xda24260, v14
	v_pk_mul_f32 v[14:15], v[16:17], v[18:19]
	v_sub_f32_e32 v16, v22, v28
	v_sub_f32_e32 v17, v24, v28
	v_mul_f32_e32 v16, 0x3fb8aa3b, v16
	v_mul_f32_e32 v17, 0x3fb8aa3b, v17
	v_exp_f32_e32 v16, v16
	v_exp_f32_e32 v17, v17
	v_add_f32_e32 v15, 0, v15
	v_mov_b32_e32 v24, v23
	v_add_f32_e32 v20, v14, v15
	v_pk_mul_f32 v[14:15], v[16:17], v[24:25]
	v_sub_f32_e32 v21, v40, v28
	v_add_f32_e32 v14, v14, v20
	v_add_f32_e32 v15, v14, v15
	v_sub_f32_e32 v14, v26, v28
	v_mul_f32_e32 v14, 0x3fb8aa3b, v14
	v_exp_f32_e32 v22, v14
	v_sub_f32_e32 v14, v38, v28
	v_mul_f32_e32 v14, 0x3fb8aa3b, v14
	v_exp_f32_e32 v23, v14
	v_mov_b32_e32 v38, v27
	v_mul_f32_e32 v21, 0x3fb8aa3b, v21
	ds_read_b32 v24, v5 offset:24808
	ds_read_b32 v20, v5 offset:25864
	ds_read_b32 v14, v5 offset:26920
	ds_read_b32 v37, v5 offset:27976
	ds_read_b32 v35, v5 offset:29032
	ds_read_b32 v33, v5 offset:30088
	ds_read_b32 v31, v5 offset:31144
	ds_read_b32 v29, v5 offset:32200
	v_pk_mul_f32 v[26:27], v[22:23], v[38:39]
	v_lshlrev_b32_e32 v98, 1, v1
	v_add_f32_e32 v15, v15, v26
	v_exp_f32_e32 v26, v21
	v_sub_f32_e32 v21, v42, v28
	v_mul_f32_e32 v21, 0x3fb8aa3b, v21
	v_add_f32_e32 v15, v15, v27
	v_exp_f32_e32 v27, v21
	v_add_u32_e32 v21, s11, v102
	v_add_u32_e32 v21, 64, v21
	ds_read2st64_b32 v[38:39], v21 offset0:44 offset1:48
	v_mov_b32_e32 v42, v41
	v_pk_mul_f32 v[40:41], v[26:27], v[42:43]
	ds_read2st64_b32 v[42:43], v21 offset0:52 offset1:56
	v_add_f32_e32 v15, v15, v40
	v_add_f32_e32 v45, v15, v41
	ds_read2st64_b32 v[40:41], v21 offset0:60 offset1:64
	s_waitcnt lgkmcnt(0)
	v_add_f32_e32 v15, 0, v38
	v_add_f32_e32 v15, v15, v39
	ds_read2st64_b32 v[38:39], v21 offset0:68 offset1:72
	v_add_f32_e32 v15, v15, v42
	v_add_f32_e32 v15, v15, v43
	v_add_f32_e32 v15, v15, v40
	s_waitcnt lgkmcnt(0)
	v_mov_b32_e32 v42, v39
	s_waitcnt vmcnt(0)
	v_mul_f32_e32 v2, 0xbfb8aa3b, v2
	v_exp_f32_e32 v43, v2
	v_add_f32_e32 v2, v15, v41
	v_add_f32_e32 v100, v2, v38
	ds_read_b32 v36, v5 offset:19528
	ds_read_b32 v34, v5 offset:20584
	ds_read_b32 v32, v5 offset:21640
	ds_read_b32 v30, v5 offset:22696
	ds_read_b32 v28, v5 offset:23752
	ds_read_b32 v25, v5 offset:33256
	ds_read_b32 v21, v5 offset:34312
	ds_read_b32 v15, v5 offset:35368
	v_pk_add_f32 v[38:39], v[100:101], v[42:43]
	v_max_f32_e32 v5, 0xda24260, v45
	v_div_scale_f32 v2, s[6:7], v39, v39, 1.0
	v_rcp_f32_e32 v40, v2
	v_mul_f32_e32 v4, 0xbfb8aa3b, v4
	v_fma_f32 v41, -v2, v40, 1.0
	v_fmac_f32_e32 v40, v41, v40
	v_div_scale_f32 v41, vcc, 1.0, v39, 1.0
	v_mul_f32_e32 v42, v41, v40
	v_fma_f32 v43, -v2, v42, v41
	v_fmac_f32_e32 v42, v43, v40
	v_fma_f32 v2, -v2, v42, v41
	v_div_fmas_f32 v2, v2, v40, v42
	v_div_fixup_f32 v39, v2, v39, 1.0
	v_mul_f32_e32 v40, 0xbfb8aa3b, v3
	v_mov_b32_e32 v2, v7
	v_mov_b32_e32 v3, v19
	s_waitcnt lgkmcnt(7)
	v_pk_fma_f32 v[2:3], v[36:37], v[2:3], 0 op_sel_hi:[1,1,0]
	v_mov_b32_e32 v7, v18
	s_waitcnt lgkmcnt(6)
	v_pk_fma_f32 v[2:3], v[34:35], v[6:7], v[2:3]
	v_mov_b32_e32 v6, v8
	v_mov_b32_e32 v7, v16
	s_waitcnt lgkmcnt(5)
	v_pk_fma_f32 v[2:3], v[6:7], v[32:33], v[2:3]
	v_mov_b32_e32 v16, v9
	s_waitcnt lgkmcnt(4)
	v_pk_fma_f32 v[2:3], v[16:17], v[30:31], v[2:3]
	v_mov_b32_e32 v6, v10
	v_mov_b32_e32 v7, v22
	s_waitcnt lgkmcnt(3)
	v_pk_fma_f32 v[2:3], v[6:7], v[28:29], v[2:3]
	v_mov_b32_e32 v22, v11
	s_waitcnt lgkmcnt(2)
	v_pk_fma_f32 v[2:3], v[22:23], v[24:25], v[2:3]
	v_mov_b32_e32 v6, v12
	v_mov_b32_e32 v7, v26
	s_waitcnt lgkmcnt(1)
	v_pk_fma_f32 v[2:3], v[6:7], v[20:21], v[2:3]
	v_mov_b32_e32 v26, v13
	s_waitcnt lgkmcnt(0)
	v_pk_fma_f32 v[2:3], v[26:27], v[14:15], v[2:3]
	v_exp_f32_e32 v7, v4
	v_div_scale_f32 v8, s[6:7], v5, v5, v3
	v_rcp_f32_e32 v9, v8
	v_exp_f32_e32 v6, v40
	v_fma_f32 v4, -v8, v9, 1.0
	v_fmac_f32_e32 v9, v4, v9
	v_div_scale_f32 v4, vcc, v3, v5, v3
	v_mul_f32_e32 v10, v4, v9
	v_fma_f32 v11, -v8, v10, v4
	v_fmac_f32_e32 v10, v11, v9
	v_fma_f32 v4, -v8, v10, v4
	v_div_scale_f32 v8, s[6:7], v44, v44, v2
	v_rcp_f32_e32 v11, v8
	v_div_fmas_f32 v4, v4, v9, v10
	v_div_fixup_f32 v3, v4, v5, v3
	v_fma_f32 v4, -v8, v11, 1.0
	v_fmac_f32_e32 v11, v4, v11
	v_div_scale_f32 v4, vcc, v2, v44, v2
	v_mul_f32_e32 v9, v4, v11
	v_fma_f32 v5, -v8, v9, v4
	v_fmac_f32_e32 v9, v5, v11
	v_fma_f32 v8, -v8, v9, v4
	v_pk_add_f32 v[4:5], v[6:7], 1.0 op_sel_hi:[1,0]
	v_div_fmas_f32 v8, v8, v11, v9
	v_div_scale_f32 v6, s[6:7], v5, v5, 1.0
	v_rcp_f32_e32 v7, v6
	v_div_fixup_f32 v2, v8, v44, v2
	v_fma_f32 v8, -v6, v7, 1.0
	v_fmac_f32_e32 v7, v8, v7
	v_div_scale_f32 v8, vcc, 1.0, v5, 1.0
	v_mul_f32_e32 v9, v8, v7
	v_fma_f32 v10, -v6, v9, v8
	v_fmac_f32_e32 v9, v10, v7
	v_fma_f32 v6, -v6, v9, v8
	v_div_scale_f32 v8, s[6:7], v4, v4, 1.0
	v_rcp_f32_e32 v10, v8
	v_div_fmas_f32 v6, v6, v7, v9
	v_div_fixup_f32 v5, v6, v5, 1.0
	s_lshl_b32 s6, s5, 6
	v_fma_f32 v6, -v8, v10, 1.0
	v_fmac_f32_e32 v10, v6, v10
	v_div_scale_f32 v6, vcc, 1.0, v4, 1.0
	v_mul_f32_e32 v7, v6, v10
	v_fma_f32 v9, -v8, v7, v6
	v_fmac_f32_e32 v7, v9, v10
	v_fma_f32 v6, -v8, v7, v6
	v_div_fmas_f32 v6, v6, v10, v7
	v_div_fixup_f32 v4, v6, v4, 1.0
	s_ashr_i32 s7, s6, 31
	v_pk_mul_f32 v[2:3], v[2:3], v[4:5]
	s_add_u32 s5, s66, s60
	v_fma_f32 v2, v38, v39, v2
	s_addc_u32 s8, s67, s61
	s_lshl_b64 s[6:7], s[6:7], 1
	v_add_f32_e32 v2, v2, v3
	s_add_u32 s6, s5, s6
	v_bfe_u32 v3, v2, 16, 1
	s_addc_u32 s7, s8, s7
	v_add3_u32 v4, v2, v3, s35
	v_lshl_add_u64 v[2:3], s[6:7], 0, v[98:99]
	v_add_co_u32_e32 v2, vcc, 0xdc00000, v2
	s_nop 1
	v_addc_co_u32_e32 v3, vcc, 0, v3, vcc
	global_store_short_d16_hi v[2:3], v4, off

.LBB0_5423:
	s_or_b64 exec, exec, s[8:9]
	s_lshl_b32 s30, s80, 1
	s_add_u32 s8, s68, s30
	s_addc_u32 s9, s69, 0
	v_mov_b32_e32 v2, s13
	s_add_u32 s8, s8, s49
	s_waitcnt lgkmcnt(0)
	s_barrier
	ds_read_b32 v10, v2
	v_mov_b32_e32 v2, v139
	s_addc_u32 s9, s9, 0
	s_add_u32 s31, s8, 0x27800000
	v_ashrrev_i32_e32 v4, 5, v2
	v_lshlrev_b32_e32 v6, 3, v4
	s_addc_u32 s42, s9, 0
	v_ashrrev_i32_e32 v7, 31, v6
	s_add_i32 s8, s5, 0x19404
	v_lshl_add_u64 v[6:7], v[6:7], 1, v[94:95]
	v_mov_b32_e32 v3, s8
	global_load_dwordx4 v[66:69], v[6:7], off
	global_load_dwordx4 v[70:73], v[6:7], off offset:32
	global_load_dwordx4 v[74:77], v[6:7], off offset:64
	global_load_dwordx4 v[78:81], v[6:7], off offset:96
	s_waitcnt lgkmcnt(0)
	s_barrier
	ds_read_b32 v3, v3
	v_lshlrev_b32_e32 v5, 3, v2
	v_and_b32_e32 v5, 24, v5
	v_lshlrev_b32_e32 v108, 1, v5
	v_mov_b32_e32 v109, v99
	s_waitcnt lgkmcnt(0)
	v_readfirstlane_b32 s8, v3
	s_lshl_b32 s8, s8, 6
	v_ashrrev_i32_e32 v3, 31, v2
	s_ashr_i32 s9, s8, 31
	v_lshlrev_b64 v[104:105], 9, v[2:3]
	v_ashrrev_i32_e32 v3, 2, v2
	s_lshl_b64 s[8:9], s[8:9], 9
	v_add_u32_e32 v8, s48, v3
	s_add_u32 s8, s31, s8
	v_ashrrev_i32_e32 v9, 31, v8
	s_addc_u32 s9, s42, s9
	v_lshlrev_b64 v[106:107], 9, v[8:9]
	v_lshl_add_u64 v[6:7], s[8:9], 0, v[104:105]
	v_lshl_add_u64 v[8:9], s[8:9], 0, v[106:107]
	v_lshl_add_u64 v[6:7], s[70:71], 1, v[6:7]
	v_lshl_add_u64 v[8:9], s[72:73], 1, v[8:9]
	v_lshl_add_u64 v[8:9], v[8:9], 0, v[108:109]
	s_waitcnt vmcnt(0)
	global_load_dwordx4 v[82:85], v[6:7], off
	global_load_dwordx4 v[86:89], v[8:9], off offset:256
	v_cmp_gt_i32_e32 vcc, 2, v10
	v_add_u32_e32 v159, 0x100, v34
	v_add_u32_e32 v158, 0x200, v34
	v_add_u32_e32 v157, 0x300, v34
	v_add_u32_e32 v156, 0x800, v34
	v_add_u32_e32 v155, 0x900, v34
	v_add_u32_e32 v154, 0xa00, v34
	v_add_u32_e32 v153, 0xb00, v34
	v_add_u32_e32 v152, 0x1000, v34
	v_add_u32_e32 v151, 0x1100, v34
	v_add_u32_e32 v150, 0x1200, v34
	v_add_u32_e32 v149, 0x1300, v34
	v_add_u32_e32 v148, 0x1800, v34
	v_add_u32_e32 v147, 0x1900, v34
	v_add_u32_e32 v146, 0x1a00, v34
	v_add_u32_e32 v145, 0x1b00, v34
	v_lshl_add_u32 v161, v2, 4, s85
	v_readfirstlane_b32 s43, v10
	s_and_b64 vcc, exec, vcc
	s_waitcnt vmcnt(0) lgkmcnt(0)
	ds_write_b128 v161, v[82:85]
	ds_write_b128 v161, v[86:89] offset:16384
	s_waitcnt lgkmcnt(0)
	s_barrier
	s_cbranch_vccnz .LBB0_5425
	s_add_i32 s8, s5, 0x19408
	v_mov_b32_e32 v3, s8
	ds_read_b32 v3, v3
	s_waitcnt lgkmcnt(0)
	v_readfirstlane_b32 s8, v3
	s_lshl_b32 s8, s8, 6
	s_ashr_i32 s9, s8, 31
	s_lshl_b64 s[8:9], s[8:9], 9
	s_add_u32 s8, s31, s8
	s_addc_u32 s9, s42, s9
	v_lshl_add_u64 v[6:7], s[8:9], 0, v[104:105]
	v_lshl_add_u64 v[8:9], s[8:9], 0, v[106:107]
	v_lshl_add_u64 v[6:7], s[70:71], 1, v[6:7]
	v_lshl_add_u64 v[8:9], s[72:73], 1, v[8:9]
	v_lshl_add_u64 v[8:9], v[8:9], 0, v[108:109]
	global_load_dwordx4 v[82:85], v[6:7], off
	global_load_dwordx4 v[86:89], v[8:9], off offset:256

.LBB0_5427:
	s_add_i32 s26, s28, -8
	v_mov_b32_e32 v34, s26
	ds_read_b32 v116, v34
	s_and_b32 s47, s46, 1
	s_waitcnt lgkmcnt(0)
	v_ashrrev_i32_e32 v34, 5, v116
	v_lshl_add_u32 v98, v34, 2, v165
	ds_read_b32 v34, v98
	v_lshlrev_b32_e64 v109, v116, 1
	s_waitcnt lgkmcnt(0)
	v_and_b32_e32 v34, v109, v34
	v_cmp_ne_u32_e32 vcc, 0, v34
	s_cbranch_vccz .LBB0_5436
	s_lshl_b32 s81, s47, 13
	v_add_u32_e32 v117, s81, v167
	ds_read_b128 v[34:37], v117
	ds_read_b128 v[118:121], v117 offset:2048
	ds_read_b128 v[230:233], v117 offset:512
	ds_read_b128 v[234:237], v117 offset:2560
	ds_read_b128 v[238:241], v117 offset:4096
	ds_read_b128 v[242:245], v117 offset:4608
	ds_read_b128 v[246:249], v117 offset:6144
	ds_read_b128 v[250:253], v117 offset:6656
	s_waitcnt lgkmcnt(6)
	v_mfma_f32_32x32x16_bf16 v[50:65], v[34:37], v[66:69], 0
	v_mfma_f32_32x32x16_bf16 v[50:65], v[118:121], v[70:73], v[50:65]
	s_waitcnt lgkmcnt(4)
	v_mfma_f32_32x32x16_bf16 v[34:49], v[230:233], v[66:69], 0
	v_mfma_f32_32x32x16_bf16 v[34:49], v[234:237], v[70:73], v[34:49]
	s_waitcnt lgkmcnt(3)
	v_mfma_f32_32x32x16_bf16 v[50:65], v[238:241], v[74:77], v[50:65]
	s_waitcnt lgkmcnt(2)
	v_mfma_f32_32x32x16_bf16 v[34:49], v[242:245], v[74:77], v[34:49]
	s_waitcnt lgkmcnt(1)
	v_mfma_f32_32x32x16_bf16 v[50:65], v[246:249], v[78:81], v[50:65]
	s_waitcnt lgkmcnt(0)
	v_mfma_f32_32x32x16_bf16 v[34:49], v[250:253], v[78:81], v[34:49]
	v_lshlrev_b32_e32 v116, 6, v116
	ds_read_b32 v117, v98
	v_sub_u32_e32 v98, v116, v96
	v_cvt_f32_i32_e32 v118, v98
	v_sub_u32_e32 v98, v96, v116
	v_cmp_lt_i32_e32 vcc, 62, v98
	s_waitcnt lgkmcnt(0)
	v_and_b32_e32 v109, v117, v109
	v_fma_f32 v116, v90, v118, v164
	v_sub_f32_e32 v171, v116, v168
	v_add_f32_e32 v116, v144, v171
	v_add_f32_e32 v117, v90, v116
	v_pk_add_f32 v[118:119], v[116:117], v[50:51]
	v_pk_add_f32 v[50:51], v[114:115], v[116:117] op_sel_hi:[1,0]
	v_add_f32_e32 v173, v143, v171
	v_pk_add_f32 v[116:117], v[50:51], v[52:53]
	v_add_f32_e32 v50, v111, v171
	v_add_f32_e32 v51, v90, v50
	v_add_f32_e32 v120, v144, v173
	v_pk_add_f32 v[52:53], v[50:51], v[54:55]
	v_pk_add_f32 v[50:51], v[114:115], v[50:51] op_sel_hi:[1,0]
	v_add_f32_e32 v121, v90, v120
	v_pk_add_f32 v[50:51], v[50:51], v[56:57]
	v_pk_add_f32 v[56:57], v[120:121], v[34:35]
	v_add_f32_e32 v34, v91, v120
	v_mov_b32_e32 v121, v173
	v_add_f32_e32 v54, v34, v36
	v_pk_add_f32 v[122:123], v[110:111], v[120:121]
	v_mov_b32_e32 v34, v37
	v_mov_b32_e32 v35, v38
	v_pk_add_f32 v[124:125], v[122:123], v[34:35]
	v_pk_add_f32 v[34:35], v[90:91], v[122:123] op_sel:[0,1]
	v_mov_b32_e32 v36, v39
	v_mov_b32_e32 v37, v40
	v_pk_add_f32 v[120:121], v[34:35], v[36:37]
	v_add_f32_e32 v34, v92, v171
	v_add_f32_e32 v35, v90, v34
	v_pk_add_f32 v[38:39], v[34:35], v[58:59]
	v_pk_add_f32 v[34:35], v[114:115], v[34:35] op_sel_hi:[1,0]
	v_mov_b32_e32 v172, v123
	v_pk_add_f32 v[34:35], v[34:35], v[60:61]
	v_pk_add_f32 v[60:61], v[112:113], v[172:173]
	v_mov_b32_e32 v36, v41
	v_mov_b32_e32 v37, v42
	v_pk_add_f32 v[122:123], v[60:61], v[36:37]
	v_pk_add_f32 v[36:37], v[90:91], v[60:61] op_sel:[0,1]
	v_mov_b32_e32 v40, v43
	v_mov_b32_e32 v41, v44
	v_mov_b32_e32 v172, v61
	v_cmp_ne_u32_e64 s[26:27], 0, v109
	v_pk_add_f32 v[58:59], v[36:37], v[40:41]
	v_add_f32_e32 v36, v103, v171
	v_pk_add_f32 v[42:43], v[102:103], v[172:173]
	v_mov_b32_e32 v44, v45
	v_mov_b32_e32 v45, v46
	s_and_b64 vcc, s[26:27], vcc
	v_add_f32_e32 v37, v90, v36
	v_pk_add_f32 v[60:61], v[42:43], v[44:45]
	v_pk_add_f32 v[44:45], v[90:91], v[42:43] op_sel:[0,1]
	v_add_f32_e32 v42, v110, v43
	v_cndmask_b32_e64 v43, 0, 1, vcc
	v_pk_add_f32 v[40:41], v[36:37], v[62:63]
	v_pk_add_f32 v[36:37], v[114:115], v[36:37] op_sel_hi:[1,0]
	v_mov_b32_e32 v46, v47
	v_mov_b32_e32 v47, v48
	v_cmp_ne_u32_e32 vcc, 0, v43
	v_pk_add_f32 v[36:37], v[36:37], v[64:65]
	v_pk_add_f32 v[62:63], v[44:45], v[46:47]
	s_cmp_eq_u64 vcc, exec
	v_add_f32_e32 v43, v42, v49
	s_cbranch_scc1 .LBB0_5430
	v_sub_u32_e32 v42, v98, v162
	v_cndmask_b32_e64 v64, v134, v42, s[26:27]
	v_cmp_gt_i32_e32 vcc, 0, v64
	s_or_b64 vcc, s[10:11], vcc
	v_cmp_gt_i32_e64 s[26:27], 40, v64
	v_cndmask_b32_e32 v118, v118, v132, vcc
	v_cmp_gt_i32_e32 vcc, 32, v64
	s_or_b64 vcc, s[16:17], vcc
	s_nop 0
	v_cndmask_b32_e32 v56, v56, v132, vcc
	v_cmp_gt_i32_e32 vcc, 1, v64
	s_or_b64 vcc, s[10:11], vcc
	s_nop 0
	v_cndmask_b32_e32 v119, v119, v132, vcc
	v_cmp_gt_i32_e32 vcc, 33, v64
	s_or_b64 vcc, s[16:17], vcc
	s_nop 0
	v_cndmask_b32_e32 v57, v57, v132, vcc
	v_cmp_gt_i32_e32 vcc, 2, v64
	s_or_b64 vcc, s[10:11], vcc
	s_nop 0
	v_cndmask_b32_e32 v116, v116, v132, vcc
	v_cmp_gt_i32_e32 vcc, 34, v64
	s_or_b64 vcc, s[16:17], vcc
	s_nop 0
	v_cndmask_b32_e32 v54, v54, v132, vcc
	v_cmp_gt_i32_e32 vcc, 3, v64
	s_or_b64 vcc, s[10:11], vcc
	s_nop 0
	v_cndmask_b32_e32 v117, v117, v132, vcc
	v_cmp_gt_i32_e32 vcc, 8, v64
	s_or_b64 vcc, s[12:13], vcc
	s_nop 0
	v_cndmask_b32_e32 v52, v52, v132, vcc
	v_cmp_gt_i32_e32 vcc, 35, v64
	s_or_b64 vcc, s[16:17], vcc
	s_nop 0
	v_cndmask_b32_e32 v55, v124, v132, vcc
	s_or_b64 vcc, s[14:15], s[26:27]
	v_cndmask_b32_e32 v44, v125, v132, vcc
	v_cmp_gt_i32_e32 vcc, 9, v64
	s_or_b64 vcc, s[12:13], vcc
	s_nop 0
	v_cndmask_b32_e32 v53, v53, v132, vcc
	v_cmp_gt_i32_e32 vcc, 41, v64
	s_or_b64 vcc, s[14:15], vcc
	s_nop 0
	v_cndmask_b32_e32 v45, v120, v132, vcc
	v_cmp_gt_i32_e32 vcc, 10, v64
	s_or_b64 vcc, s[12:13], vcc
	s_nop 0
	v_cndmask_b32_e32 v50, v50, v132, vcc
	v_cmp_gt_i32_e32 vcc, 42, v64
	s_or_b64 vcc, s[14:15], vcc
	s_nop 0
	v_cndmask_b32_e32 v46, v121, v132, vcc
	v_cmp_gt_i32_e32 vcc, 11, v64
	s_or_b64 vcc, s[12:13], vcc
	s_nop 0
	v_cndmask_b32_e32 v51, v51, v132, vcc
	v_cmp_gt_i32_e32 vcc, 43, v64
	s_or_b64 vcc, s[14:15], vcc
	s_nop 0
	v_cndmask_b32_e32 v47, v122, v132, vcc
	v_cmp_gt_i32_e32 vcc, 16, v64
	s_or_b64 vcc, s[18:19], vcc
	s_nop 0
	v_cndmask_b32_e32 v38, v38, v132, vcc
	v_cmp_gt_i32_e32 vcc, 48, v64
	s_or_b64 vcc, s[20:21], vcc
	s_nop 0
	v_cndmask_b32_e32 v48, v123, v132, vcc
	v_cmp_gt_i32_e32 vcc, 17, v64
	s_or_b64 vcc, s[18:19], vcc
	s_nop 0
	v_cndmask_b32_e32 v39, v39, v132, vcc
	v_cmp_gt_i32_e32 vcc, 49, v64
	s_or_b64 vcc, s[20:21], vcc
	s_nop 0
	v_cndmask_b32_e32 v49, v58, v132, vcc
	v_cmp_gt_i32_e32 vcc, 18, v64
	s_or_b64 vcc, s[18:19], vcc
	s_nop 0
	v_cndmask_b32_e32 v34, v34, v132, vcc
	v_cmp_gt_i32_e32 vcc, 50, v64
	s_or_b64 vcc, s[20:21], vcc
	s_nop 0
	v_cndmask_b32_e32 v58, v59, v132, vcc
	v_cmp_gt_i32_e32 vcc, 19, v64
	s_or_b64 vcc, s[18:19], vcc
	s_nop 0
	v_cndmask_b32_e32 v35, v35, v132, vcc
	v_cmp_gt_i32_e32 vcc, 51, v64
	s_or_b64 vcc, s[20:21], vcc
	s_nop 0
	v_cndmask_b32_e32 v59, v60, v132, vcc
	v_cmp_gt_i32_e32 vcc, 24, v64
	s_or_b64 vcc, s[22:23], vcc
	s_nop 0
	v_cndmask_b32_e32 v40, v40, v132, vcc
	v_cmp_gt_i32_e32 vcc, 56, v64
	s_or_b64 vcc, s[24:25], vcc
	s_nop 0
	v_cndmask_b32_e32 v60, v61, v132, vcc
	v_cmp_gt_i32_e32 vcc, 25, v64
	s_or_b64 vcc, s[22:23], vcc
	s_nop 0
	v_cndmask_b32_e32 v41, v41, v132, vcc
	v_cmp_gt_i32_e32 vcc, 57, v64
	s_or_b64 vcc, s[24:25], vcc
	s_nop 0
	v_cndmask_b32_e32 v61, v62, v132, vcc
	v_cmp_gt_i32_e32 vcc, 26, v64
	s_or_b64 vcc, s[22:23], vcc
	s_nop 0
	v_cndmask_b32_e32 v36, v36, v132, vcc
	v_cmp_gt_i32_e32 vcc, 58, v64
	s_or_b64 vcc, s[24:25], vcc
	s_nop 0
	v_cndmask_b32_e32 v42, v63, v132, vcc
	v_cmp_gt_i32_e32 vcc, 27, v64
	s_or_b64 vcc, s[22:23], vcc
	s_nop 0
	v_cndmask_b32_e32 v37, v37, v132, vcc
	v_cmp_gt_i32_e32 vcc, 59, v64
	s_or_b64 vcc, s[24:25], vcc
	s_nop 0
	v_cndmask_b32_e32 v43, v43, v132, vcc
	s_branch .LBB0_5431

.LBB0_5438:
	s_add_i32 s27, s46, 2
	s_cmp_ge_i32 s27, s43
	s_waitcnt lgkmcnt(0)
	s_barrier
	s_cbranch_scc1 .LBB0_5440
	v_mov_b32_e32 v34, s28
	ds_read_b32 v34, v34
	v_mov_b32_e32 v109, v99
	s_waitcnt lgkmcnt(0)
	v_readfirstlane_b32 s27, v34
	s_lshl_b32 s46, s27, 6
	s_ashr_i32 s47, s46, 31
	s_lshl_b64 s[46:47], s[46:47], 9
	s_add_u32 s46, s31, s46
	s_addc_u32 s47, s42, s47
	v_lshl_add_u64 v[34:35], s[46:47], 0, v[104:105]
	v_lshl_add_u64 v[36:37], s[46:47], 0, v[106:107]
	v_lshl_add_u64 v[34:35], s[70:71], 1, v[34:35]
	v_lshl_add_u64 v[36:37], s[72:73], 1, v[36:37]
	v_lshl_add_u64 v[36:37], v[36:37], 0, v[108:109]
	s_waitcnt vmcnt(0)
	global_load_dwordx4 v[82:85], v[34:35], off
	global_load_dwordx4 v[86:89], v[36:37], off offset:256

.LBB0_5480:
	s_or_b64 exec, exec, s[10:11]
	s_and_saveexec_b64 s[8:9], s[6:7]
	ds_write_b32 v141, v35 offset:33024
	s_or_b64 exec, exec, s[8:9]
	s_waitcnt lgkmcnt(0)
	ds_read_b32 v36, v1 offset:33024
	ds_read2_b32 v[34:35], v142 offset1:32
	v_add_u32_e32 v106, 0x9000, v159
	v_add_u32_e32 v107, 0x9000, v158
	v_add_u32_e32 v108, 0x9000, v157
	v_add_u32_e32 v109, 0x9000, v156
	s_waitcnt lgkmcnt(0)
	v_fma_f32 v18, v18, v36, v34
	v_fmac_f32_e32 v35, v2, v36
	ds_write2_b32 v142, v18, v35 offset1:32
	ds_read_b32 v2, v1 offset:33028
	ds_read2_b32 v[34:35], v106 offset1:32
	v_add_u32_e32 v110, 0x9000, v155
	v_add_u32_e32 v112, 0x9000, v154
	v_add_u32_e32 v113, 0x9000, v153
	v_add_u32_e32 v114, 0x9000, v152
	s_waitcnt lgkmcnt(0)
	v_fma_f32 v18, v19, v2, v34
	v_fmac_f32_e32 v35, v3, v2
	ds_write2_b32 v106, v18, v35 offset1:32
	ds_read_b32 v18, v1 offset:33032
	ds_read2_b32 v[2:3], v107 offset1:32
	v_add_u32_e32 v115, 0x9000, v151
	v_add_u32_e32 v117, 0x9000, v150
	v_add_u32_e32 v118, 0x9000, v149
	v_add_u32_e32 v91, 0x9000, v148
	s_waitcnt lgkmcnt(0)
	v_fma_f32 v2, v20, v18, v2
	v_fmac_f32_e32 v3, v4, v18
	ds_write2_b32 v107, v2, v3 offset1:32
	ds_read_b32 v4, v1 offset:33036
	ds_read2_b32 v[2:3], v108 offset1:32
	v_add_u32_e32 v102, 0x9000, v147
	v_add_u32_e32 v111, 0x9000, v146
	v_add_u32_e32 v116, 0x9000, v145
	s_add_u32 s8, s68, s30
	s_waitcnt lgkmcnt(0)
	v_fma_f32 v2, v21, v4, v2
	v_fmac_f32_e32 v3, v5, v4
	ds_write2_b32 v108, v2, v3 offset1:32
	ds_read_b32 v4, v1 offset:33056
	ds_read2_b32 v[2:3], v109 offset1:32
	s_addc_u32 s9, s69, 0
	s_add_u32 s8, s8, s49
	s_addc_u32 s9, s9, 0
	s_add_u32 s12, s8, 0x28000000
	s_waitcnt lgkmcnt(0)
	v_fma_f32 v2, v22, v4, v2
	v_fmac_f32_e32 v3, v6, v4
	ds_write2_b32 v109, v2, v3 offset1:32
	ds_read_b32 v4, v1 offset:33060
	ds_read2_b32 v[2:3], v110 offset1:32
	s_addc_u32 s13, s9, 0
	s_lshl_b32 s10, s65, 15
	s_add_u32 s8, s12, s10
	s_addc_u32 s9, s13, 0
	s_waitcnt lgkmcnt(0)
	v_fma_f32 v2, v23, v4, v2
	v_fmac_f32_e32 v3, v7, v4
	ds_write2_b32 v110, v2, v3 offset1:32
	ds_read_b32 v4, v1 offset:33064
	ds_read2_b32 v[2:3], v112 offset1:32
	s_cmp_eq_u32 s65, 0
	s_waitcnt lgkmcnt(0)
	v_fma_f32 v2, v24, v4, v2
	v_fmac_f32_e32 v3, v8, v4
	ds_write2_b32 v112, v2, v3 offset1:32
	ds_read_b32 v4, v1 offset:33068
	ds_read2_b32 v[2:3], v113 offset1:32
	s_waitcnt lgkmcnt(0)
	v_fma_f32 v2, v25, v4, v2
	v_fmac_f32_e32 v3, v9, v4
	ds_write2_b32 v113, v2, v3 offset1:32
	ds_read_b32 v4, v1 offset:33088
	ds_read2_b32 v[2:3], v114 offset1:32
	s_waitcnt lgkmcnt(0)
	v_fma_f32 v2, v26, v4, v2
	v_fmac_f32_e32 v3, v10, v4
	ds_write2_b32 v114, v2, v3 offset1:32
	ds_read_b32 v4, v1 offset:33092
	ds_read2_b32 v[2:3], v115 offset1:32
	s_waitcnt lgkmcnt(0)
	v_fma_f32 v2, v27, v4, v2
	v_fmac_f32_e32 v3, v11, v4
	ds_write2_b32 v115, v2, v3 offset1:32
	ds_read_b32 v4, v1 offset:33096
	ds_read2_b32 v[2:3], v117 offset1:32
	s_waitcnt lgkmcnt(0)
	v_fma_f32 v2, v28, v4, v2
	v_fmac_f32_e32 v3, v12, v4
	ds_write2_b32 v117, v2, v3 offset1:32
	ds_read_b32 v4, v1 offset:33100
	ds_read2_b32 v[2:3], v118 offset1:32
	s_waitcnt lgkmcnt(0)
	v_fma_f32 v2, v29, v4, v2
	v_fmac_f32_e32 v3, v13, v4
	ds_write2_b32 v118, v2, v3 offset1:32
	ds_read_b32 v4, v1 offset:33120
	ds_read2_b32 v[2:3], v91 offset1:32
	s_waitcnt lgkmcnt(0)
	v_fma_f32 v2, v30, v4, v2
	v_fmac_f32_e32 v3, v14, v4
	ds_write2_b32 v91, v2, v3 offset1:32
	ds_read_b32 v4, v1 offset:33124
	ds_read2_b32 v[2:3], v102 offset1:32
	s_waitcnt lgkmcnt(0)
	v_fma_f32 v2, v31, v4, v2
	v_fmac_f32_e32 v3, v15, v4
	ds_write2_b32 v102, v2, v3 offset1:32
	ds_read_b32 v4, v1 offset:33128
	ds_read2_b32 v[2:3], v111 offset1:32
	s_waitcnt lgkmcnt(0)
	v_fma_f32 v2, v32, v4, v2
	v_fmac_f32_e32 v3, v16, v4
	ds_write2_b32 v111, v2, v3 offset1:32
	ds_read_b32 v4, v1 offset:33132
	ds_read2_b32 v[2:3], v116 offset1:32
	s_waitcnt lgkmcnt(0)
	v_fma_f32 v2, v33, v4, v2
	v_fmac_f32_e32 v3, v17, v4
	ds_write2_b32 v116, v2, v3 offset1:32
	v_mov_b32_e32 v2, v139
	s_waitcnt lgkmcnt(0)
	s_nop 0
	v_ashrrev_i32_e32 v4, 5, v2
	v_lshlrev_b32_e32 v3, 3, v2
	v_lshlrev_b32_e32 v6, 3, v4
	v_and_b32_e32 v5, 24, v3
	v_ashrrev_i32_e32 v7, 31, v6
	v_ashrrev_i32_e32 v3, 31, v2
	v_lshl_add_u64 v[6:7], v[6:7], 1, v[94:95]
	v_lshlrev_b64 v[94:95], 9, v[2:3]
	global_load_dwordx4 v[66:69], v[6:7], off
	global_load_dwordx4 v[70:73], v[6:7], off offset:32
	global_load_dwordx4 v[74:77], v[6:7], off offset:64
	global_load_dwordx4 v[78:81], v[6:7], off offset:96
	v_lshl_add_u64 v[6:7], s[8:9], 0, v[94:95]
	v_lshl_add_u64 v[6:7], s[70:71], 1, v[6:7]
	v_ashrrev_i32_e32 v3, 2, v2
	s_waitcnt lgkmcnt(0)
	s_barrier
	s_waitcnt vmcnt(0)
	global_load_dwordx4 v[82:85], v[6:7], off
	v_add_u32_e32 v6, s48, v3
	v_ashrrev_i32_e32 v7, 31, v6
	v_lshlrev_b64 v[96:97], 9, v[6:7]
	v_lshl_add_u64 v[6:7], s[8:9], 0, v[96:97]
	v_lshl_add_u64 v[6:7], s[72:73], 1, v[6:7]
	v_lshlrev_b32_e32 v98, 1, v5
	v_lshl_add_u64 v[6:7], v[6:7], 0, v[98:99]
	global_load_dwordx4 v[86:89], v[6:7], off offset:256
	v_lshl_add_u32 v119, v2, 4, s85
	s_waitcnt vmcnt(0) lgkmcnt(0)
	ds_write_b128 v119, v[82:85]
	ds_write_b128 v119, v[86:89] offset:16384
	s_waitcnt lgkmcnt(0)
	s_barrier
	s_cbranch_scc1 .LBB0_5484
	s_lshl_b32 s8, s52, 9
	s_add_u32 s8, s12, s8
	s_addc_u32 s9, s13, 0
	s_add_u32 s8, s8, 0xffff8000
	s_addc_u32 s9, s9, -1
	v_lshl_add_u64 v[6:7], s[8:9], 0, v[94:95]
	v_lshl_add_u64 v[8:9], s[8:9], 0, v[96:97]
	v_lshl_add_u64 v[6:7], s[70:71], 1, v[6:7]
	v_lshl_add_u64 v[8:9], s[72:73], 1, v[8:9]
	v_lshl_add_u64 v[8:9], v[8:9], 0, v[98:99]
	global_load_dwordx4 v[82:85], v[6:7], off
	global_load_dwordx4 v[86:89], v[8:9], off offset:256

.LBB0_5499:
	s_or_b64 exec, exec, s[8:9]
	s_and_saveexec_b64 s[8:9], s[6:7]
	ds_write_b32 v141, v35 offset:33024
	s_or_b64 exec, exec, s[8:9]
	s_waitcnt lgkmcnt(0)
	ds_read_b32 v38, v1 offset:33024
	ds_read2_b32 v[34:35], v142 offset1:32
	ds_read2_b32 v[36:37], v106 offset1:32
	s_or_b32 s6, s50, s52
	s_add_u32 s6, s6, s70
	s_addc_u32 s7, 0, s71
	s_waitcnt lgkmcnt(0)
	v_fma_f32 v18, v18, v38, v34
	v_fmac_f32_e32 v35, v2, v38
	ds_write2_b32 v142, v18, v35 offset1:32
	ds_read_b32 v2, v1 offset:33028
	ds_read2_b32 v[34:35], v107 offset1:32
	s_mov_b64 s[8:9], 0xdc00000
	s_waitcnt lgkmcnt(0)
	v_fma_f32 v18, v19, v2, v36
	v_fmac_f32_e32 v37, v3, v2
	ds_write2_b32 v106, v18, v37 offset1:32
	ds_read_b32 v18, v1 offset:33032
	ds_read2_b32 v[2:3], v108 offset1:32
	s_waitcnt lgkmcnt(0)
	v_fma_f32 v19, v20, v18, v34
	v_fmac_f32_e32 v35, v4, v18
	ds_write2_b32 v107, v19, v35 offset1:32
	ds_read_b32 v4, v1 offset:33036
	ds_read2_b32 v[18:19], v109 offset1:32
	s_waitcnt lgkmcnt(0)
	v_fma_f32 v2, v21, v4, v2
	v_fmac_f32_e32 v3, v5, v4
	ds_write2_b32 v108, v2, v3 offset1:32
	ds_read_b32 v4, v1 offset:33056
	ds_read2_b32 v[2:3], v110 offset1:32
	s_waitcnt lgkmcnt(0)
	v_fma_f32 v5, v22, v4, v18
	v_fmac_f32_e32 v19, v6, v4
	ds_write2_b32 v109, v5, v19 offset1:32
	ds_read_b32 v6, v1 offset:33060
	ds_read2_b32 v[4:5], v112 offset1:32
	s_waitcnt lgkmcnt(0)
	v_fma_f32 v2, v23, v6, v2
	v_fmac_f32_e32 v3, v7, v6
	ds_write2_b32 v110, v2, v3 offset1:32
	ds_read_b32 v6, v1 offset:33064
	ds_read2_b32 v[2:3], v113 offset1:32
	v_lshlrev_b32_e32 v7, 3, v139
	s_waitcnt lgkmcnt(0)
	v_fma_f32 v4, v24, v6, v4
	v_fmac_f32_e32 v5, v8, v6
	ds_write2_b32 v112, v4, v5 offset1:32
	ds_read_b32 v6, v1 offset:33068
	ds_read2_b32 v[4:5], v114 offset1:32
	v_and_or_b32 v8, v93, 3, s77
	v_lshlrev_b32_e32 v98, 7, v8
	s_waitcnt lgkmcnt(0)
	v_fma_f32 v2, v25, v6, v2
	v_fmac_f32_e32 v3, v9, v6
	ds_write2_b32 v113, v2, v3 offset1:32
	ds_read_b32 v6, v1 offset:33088
	ds_read2_b32 v[2:3], v115 offset1:32
	v_and_b32_e32 v9, 56, v7
	s_waitcnt lgkmcnt(0)
	v_fma_f32 v4, v26, v6, v4
	v_fmac_f32_e32 v5, v10, v6
	ds_write2_b32 v114, v4, v5 offset1:32
	ds_read_b32 v6, v1 offset:33092
	ds_read2_b32 v[4:5], v117 offset1:32
	s_waitcnt lgkmcnt(0)
	v_fma_f32 v2, v27, v6, v2
	v_fmac_f32_e32 v3, v11, v6
	ds_write2_b32 v115, v2, v3 offset1:32
	ds_read_b32 v6, v1 offset:33096
	ds_read2_b32 v[2:3], v118 offset1:32
	s_waitcnt lgkmcnt(0)
	v_fma_f32 v4, v28, v6, v4
	v_fmac_f32_e32 v5, v12, v6
	ds_write2_b32 v117, v4, v5 offset1:32
	ds_read_b32 v6, v1 offset:33100
	ds_read2_b32 v[4:5], v91 offset1:32
	s_waitcnt lgkmcnt(0)
	v_fma_f32 v2, v29, v6, v2
	v_fmac_f32_e32 v3, v13, v6
	ds_write2_b32 v118, v2, v3 offset1:32
	ds_read_b32 v6, v1 offset:33120
	ds_read2_b32 v[2:3], v102 offset1:32
	s_waitcnt lgkmcnt(0)
	v_fma_f32 v4, v30, v6, v4
	v_fmac_f32_e32 v5, v14, v6
	ds_write2_b32 v91, v4, v5 offset1:32
	ds_read_b32 v6, v1 offset:33124
	ds_read2_b32 v[4:5], v111 offset1:32
	v_lshl_add_u32 v14, v9, 2, s54
	v_lshl_add_u32 v8, v93, 8, v14
	s_waitcnt lgkmcnt(0)
	v_fma_f32 v2, v31, v6, v2
	v_fmac_f32_e32 v3, v15, v6
	ds_write2_b32 v102, v2, v3 offset1:32
	ds_read_b32 v6, v1 offset:33128
	ds_read2_b32 v[2:3], v116 offset1:32
	s_waitcnt lgkmcnt(0)
	v_fma_f32 v4, v32, v6, v4
	v_fmac_f32_e32 v5, v16, v6
	ds_write2_b32 v111, v4, v5 offset1:32
	ds_read_b32 v1, v1 offset:33132
	v_lshl_add_u64 v[6:7], s[68:69], 0, v[98:99]
	v_lshlrev_b32_e32 v98, 1, v9
	v_lshl_add_u64 v[6:7], v[6:7], 0, v[98:99]
	v_lshl_add_u64 v[6:7], v[6:7], 0, s[8:9]
	s_waitcnt lgkmcnt(0)
	v_fma_f32 v2, v33, v1, v2
	v_fmac_f32_e32 v3, v17, v1
	ds_write2_b32 v116, v2, v3 offset1:32
	s_waitcnt lgkmcnt(0)
	ds_read_b128 v[2:5], v8 offset:36864
	ds_read_b128 v[8:11], v8 offset:36880
	s_waitcnt lgkmcnt(0)
	v_bfe_u32 v1, v2, 16, 1
	v_bfe_u32 v12, v3, 16, 1
	v_add3_u32 v1, v2, v1, s35
	v_bfe_u32 v13, v4, 16, 1
	v_bfe_u32 v15, v5, 16, 1
	v_bfe_u32 v16, v8, 16, 1
	v_bfe_u32 v17, v9, 16, 1
	v_bfe_u32 v18, v10, 16, 1
	v_add3_u32 v2, v3, v12, s35
	v_lshrrev_b32_e32 v1, 16, v1
	v_bfe_u32 v19, v11, 16, 1
	v_add3_u32 v3, v4, v13, s35
	v_add3_u32 v4, v5, v15, s35
	v_add3_u32 v5, v8, v16, s35
	v_add3_u32 v8, v9, v17, s35
	v_add3_u32 v9, v10, v18, s35
	v_and_or_b32 v2, v2, s45, v1
	v_lshrrev_b32_e32 v1, 5, v139
	v_add3_u32 v10, v11, v19, s35
	v_lshrrev_b32_e32 v3, 16, v3
	v_lshrrev_b32_e32 v5, 16, v5
	v_lshrrev_b32_e32 v9, 16, v9
	v_or_b32_e32 v12, s6, v1
	v_mov_b32_e32 v13, s7
	v_and_or_b32 v3, v4, s45, v3
	v_and_or_b32 v4, v8, s45, v5
	v_and_or_b32 v5, v10, s45, v9
	v_lshlrev_b64 v[8:9], 11, v[12:13]
	v_lshl_add_u64 v[8:9], v[6:7], 0, v[8:9]
	v_or_b32_e32 v1, 8, v93
	global_store_dwordx4 v[8:9], v[2:5], off
	v_lshl_add_u32 v8, v1, 8, v14
	ds_read_b128 v[2:5], v8 offset:36864
	ds_read_b128 v[8:11], v8 offset:36880
	v_lshrrev_b32_e32 v1, 2, v1
	s_waitcnt lgkmcnt(0)
	v_bfe_u32 v12, v2, 16, 1
	v_add3_u32 v2, v2, v12, s35
	v_bfe_u32 v12, v3, 16, 1
	v_lshrrev_b32_e32 v2, 16, v2
	v_add3_u32 v3, v3, v12, s35
	v_and_or_b32 v2, v3, s45, v2
	v_bfe_u32 v3, v4, 16, 1
	v_add3_u32 v3, v4, v3, s35
	v_bfe_u32 v4, v5, 16, 1
	v_lshrrev_b32_e32 v3, 16, v3
	v_add3_u32 v4, v5, v4, s35
	v_and_or_b32 v3, v4, s45, v3
	v_bfe_u32 v4, v8, 16, 1
	v_add3_u32 v4, v8, v4, s35
	v_bfe_u32 v5, v9, 16, 1
	v_lshrrev_b32_e32 v4, 16, v4
	v_add3_u32 v5, v9, v5, s35
	v_and_or_b32 v4, v5, s45, v4
	v_bfe_u32 v5, v10, 16, 1
	v_add3_u32 v5, v10, v5, s35
	v_bfe_u32 v8, v11, 16, 1
	v_lshrrev_b32_e32 v5, 16, v5
	v_add3_u32 v8, v11, v8, s35
	v_or_b32_e32 v12, s6, v1
	v_and_or_b32 v5, v8, s45, v5
	v_lshlrev_b64 v[8:9], 11, v[12:13]
	v_lshl_add_u64 v[8:9], v[6:7], 0, v[8:9]
	v_or_b32_e32 v1, 16, v93
	global_store_dwordx4 v[8:9], v[2:5], off
	v_lshl_add_u32 v8, v1, 8, v14
	ds_read_b128 v[2:5], v8 offset:36864
	ds_read_b128 v[8:11], v8 offset:36880
	v_lshrrev_b32_e32 v1, 2, v1
	s_waitcnt lgkmcnt(0)
	v_bfe_u32 v12, v2, 16, 1
	v_add3_u32 v2, v2, v12, s35
	v_bfe_u32 v12, v3, 16, 1
	v_lshrrev_b32_e32 v2, 16, v2
	v_add3_u32 v3, v3, v12, s35
	v_and_or_b32 v2, v3, s45, v2
	v_bfe_u32 v3, v4, 16, 1
	v_add3_u32 v3, v4, v3, s35
	v_bfe_u32 v4, v5, 16, 1
	v_lshrrev_b32_e32 v3, 16, v3
	v_add3_u32 v4, v5, v4, s35
	v_and_or_b32 v3, v4, s45, v3
	v_bfe_u32 v4, v8, 16, 1
	v_add3_u32 v4, v8, v4, s35
	v_bfe_u32 v5, v9, 16, 1
	v_lshrrev_b32_e32 v4, 16, v4
	v_add3_u32 v5, v9, v5, s35
	v_and_or_b32 v4, v5, s45, v4
	v_bfe_u32 v5, v10, 16, 1
	v_add3_u32 v5, v10, v5, s35
	v_bfe_u32 v8, v11, 16, 1
	v_lshrrev_b32_e32 v5, 16, v5
	v_add3_u32 v8, v11, v8, s35
	v_or_b32_e32 v12, s6, v1
	v_and_or_b32 v5, v8, s45, v5
	v_lshlrev_b64 v[8:9], 11, v[12:13]
	v_lshl_add_u64 v[8:9], v[6:7], 0, v[8:9]
	v_or_b32_e32 v1, 24, v93
	global_store_dwordx4 v[8:9], v[2:5], off
	v_lshl_add_u32 v8, v1, 8, v14
	ds_read_b128 v[2:5], v8 offset:36864
	ds_read_b128 v[8:11], v8 offset:36880
	v_lshrrev_b32_e32 v1, 2, v1
	s_waitcnt lgkmcnt(0)
	v_bfe_u32 v12, v2, 16, 1
	v_add3_u32 v2, v2, v12, s35
	v_bfe_u32 v12, v3, 16, 1
	v_lshrrev_b32_e32 v2, 16, v2
	v_add3_u32 v3, v3, v12, s35
	v_and_or_b32 v2, v3, s45, v2
	v_bfe_u32 v3, v4, 16, 1
	v_add3_u32 v3, v4, v3, s35
	v_bfe_u32 v4, v5, 16, 1
	v_lshrrev_b32_e32 v3, 16, v3
	v_add3_u32 v4, v5, v4, s35
	v_and_or_b32 v3, v4, s45, v3
	v_bfe_u32 v4, v8, 16, 1
	v_add3_u32 v4, v8, v4, s35
	v_bfe_u32 v5, v9, 16, 1
	v_lshrrev_b32_e32 v4, 16, v4
	v_add3_u32 v5, v9, v5, s35
	v_and_or_b32 v4, v5, s45, v4
	v_bfe_u32 v5, v10, 16, 1
	v_add3_u32 v5, v10, v5, s35
	v_bfe_u32 v8, v11, 16, 1
	v_lshrrev_b32_e32 v5, 16, v5
	v_add3_u32 v8, v11, v8, s35
	v_or_b32_e32 v12, s6, v1
	v_and_or_b32 v5, v8, s45, v5
	v_lshlrev_b64 v[8:9], 11, v[12:13]
	v_lshl_add_u64 v[6:7], v[6:7], 0, v[8:9]
	global_store_dwordx4 v[6:7], v[2:5], off
	s_waitcnt lgkmcnt(0)
	s_waitcnt lgkmcnt(0)
	s_barrier

.LBB0_5518:
	s_add_u32 s10, s68, 0x7800000
	s_addc_u32 s11, s69, 0
	s_add_u32 s8, s68, 0xb800000
	s_addc_u32 s9, s69, 0
	s_lshl_b32 s4, s6, 8
	s_add_i32 s3, s2, 0x4000
	v_lshl_or_b32 v130, v138, 2, s4
	v_or_b32_e32 v130, s26, v130
	v_or_b32_e32 v134, s3, v1
	s_movk_i32 s4, 0x4080
	s_movk_i32 s12, 0x4000
	s_ashr_i32 s3, s3, 13
	v_cmp_gt_i32_e32 vcc, s4, v134
	v_or_b32_e32 v132, 16, v130
	s_and_saveexec_b64 s[6:7], vcc
	s_cbranch_execz .LBB0_5520
	v_readlane_b32 s14, v228, 17
	v_add_u32_e32 v131, 0xffffc002, v134
	v_mov_b32_e32 v133, s3
	v_cmp_gt_i32_e32 vcc, s12, v134
	v_readlane_b32 s15, v228, 18
	s_mov_b32 s12, 0x9000
	v_cndmask_b32_e32 v131, v131, v133, vcc
	v_mov_b64_e32 v[136:137], s[14:15]
	v_mad_i64_i32 v[136:137], s[12:13], v131, s12, v[136:137]
	s_mov_b64 s[12:13], 0x5000
	v_ashrrev_i32_e32 v135, 31, v134
	v_lshl_add_u64 v[144:145], v[136:137], 0, s[12:13]
	v_lshlrev_b64 v[136:137], 12, v[134:135]
	v_add_u32_e32 v148, 0xffffc000, v134
	v_mov_b32_e32 v149, 0
	v_lshl_add_u64 v[146:147], s[10:11], 0, v[136:137]
	v_lshlrev_b64 v[136:137], 12, v[148:149]
	v_lshl_add_u64 v[136:137], s[8:9], 0, v[136:137]
	v_mov_b32_e32 v131, v149
	v_cndmask_b32_e32 v141, v137, v147, vcc
	v_cndmask_b32_e32 v140, v136, v146, vcc
	v_lshlrev_b64 v[150:151], 2, v[130:131]
	v_lshl_add_u64 v[136:137], v[144:145], 0, v[150:151]
	v_lshl_add_u64 v[152:153], v[140:141], 0, v[150:151]
	global_load_dwordx4 v[136:139], v[136:137], off
	v_mov_b32_e32 v133, v149
	global_load_dwordx4 v[140:143], v[152:153], off
	v_lshl_add_u64 v[146:147], v[146:147], 0, v[150:151]
	v_lshl_add_u64 v[150:151], v[132:133], 2, v[144:145]
	v_or_b32_e32 v148, 0x80, v130
	s_waitcnt vmcnt(0) lgkmcnt(0)
	v_pk_fma_f32 v[128:129], v[128:129], v[138:139], v[142:143]
	v_pk_fma_f32 v[126:127], v[126:127], v[136:137], v[140:141]
	global_store_dwordx4 v[146:147], v[126:129], off
	global_load_dwordx4 v[126:129], v[150:151], off
	s_nop 0
	global_load_dwordx4 v[136:139], v[152:153], off offset:64
	v_lshl_add_u64 v[140:141], v[148:149], 2, v[144:145]
	v_or_b32_e32 v148, 0x90, v130
	s_waitcnt vmcnt(0) lgkmcnt(0)
	v_pk_fma_f32 v[124:125], v[124:125], v[128:129], v[138:139]
	v_pk_fma_f32 v[122:123], v[122:123], v[126:127], v[136:137]
	global_store_dwordx4 v[146:147], v[122:125], off offset:64
	global_load_dwordx4 v[122:125], v[140:141], off
	s_nop 0
	global_load_dwordx4 v[126:129], v[152:153], off offset:512
	v_lshl_add_u64 v[136:137], v[148:149], 2, v[144:145]
	s_waitcnt vmcnt(0) lgkmcnt(0)
	v_pk_fma_f32 v[120:121], v[120:121], v[124:125], v[128:129]
	v_pk_fma_f32 v[118:119], v[118:119], v[122:123], v[126:127]
	global_store_dwordx4 v[146:147], v[118:121], off offset:512
	global_load_dwordx4 v[118:121], v[136:137], off
	s_nop 0
	global_load_dwordx4 v[122:125], v[152:153], off offset:576
	s_waitcnt vmcnt(0) lgkmcnt(0)
	v_pk_fma_f32 v[116:117], v[116:117], v[120:121], v[124:125]
	v_pk_fma_f32 v[114:115], v[114:115], v[118:119], v[122:123]
	global_store_dwordx4 v[146:147], v[114:117], off offset:576
.LBB0_5520:
	s_or_b64 exec, exec, s[6:7]
	s_nop 0
	v_or_b32_e32 v114, 16, v134
	v_cmp_gt_i32_e32 vcc, s4, v114
	s_and_saveexec_b64 s[6:7], vcc
	s_cbranch_execz .LBB0_5522
	s_movk_i32 s4, 0x4000
	v_readlane_b32 s12, v228, 17
	v_add_u32_e32 v115, 0xffffc012, v134
	v_mov_b32_e32 v116, s3
	v_cmp_gt_i32_e32 vcc, s4, v114
	v_readlane_b32 s13, v228, 18
	s_mov_b32 s4, 0x9000
	v_cndmask_b32_e32 v115, v115, v116, vcc
	v_mov_b64_e32 v[116:117], s[12:13]
	v_mad_i64_i32 v[116:117], s[12:13], v115, s4, v[116:117]
	v_ashrrev_i32_e32 v115, 31, v114
	v_lshlrev_b64 v[114:115], 12, v[114:115]
	v_add_u32_e32 v126, 0xffffc010, v134
	v_mov_b32_e32 v127, 0
	v_lshl_add_u64 v[124:125], s[10:11], 0, v[114:115]
	v_lshlrev_b64 v[114:115], 12, v[126:127]
	s_mov_b64 s[12:13], 0x5000
	v_lshl_add_u64 v[114:115], s[8:9], 0, v[114:115]
	v_mov_b32_e32 v131, v127
	v_lshl_add_u64 v[122:123], v[116:117], 0, s[12:13]
	v_cndmask_b32_e32 v119, v115, v125, vcc
	v_cndmask_b32_e32 v118, v114, v124, vcc
	v_lshlrev_b64 v[128:129], 2, v[130:131]
	v_lshl_add_u64 v[114:115], v[122:123], 0, v[128:129]
	v_lshl_add_u64 v[136:137], v[118:119], 0, v[128:129]
	global_load_dwordx4 v[114:117], v[114:115], off
	v_mov_b32_e32 v133, v127
	global_load_dwordx4 v[118:121], v[136:137], off
	v_lshl_add_u64 v[124:125], v[124:125], 0, v[128:129]
	v_lshl_add_u64 v[128:129], v[132:133], 2, v[122:123]
	v_or_b32_e32 v126, 0x80, v130
	s_waitcnt vmcnt(0) lgkmcnt(0)
	v_pk_fma_f32 v[112:113], v[112:113], v[116:117], v[120:121]
	v_pk_fma_f32 v[110:111], v[110:111], v[114:115], v[118:119]
	global_store_dwordx4 v[124:125], v[110:113], off
	global_load_dwordx4 v[110:113], v[128:129], off
	s_nop 0
	global_load_dwordx4 v[114:117], v[136:137], off offset:64
	v_lshl_add_u64 v[118:119], v[126:127], 2, v[122:123]
	v_or_b32_e32 v126, 0x90, v130
	s_waitcnt vmcnt(0) lgkmcnt(0)
	v_pk_fma_f32 v[108:109], v[108:109], v[112:113], v[116:117]
	v_pk_fma_f32 v[106:107], v[106:107], v[110:111], v[114:115]
	global_store_dwordx4 v[124:125], v[106:109], off offset:64
	global_load_dwordx4 v[106:109], v[118:119], off
	s_nop 0
	global_load_dwordx4 v[110:113], v[136:137], off offset:512
	v_lshl_add_u64 v[114:115], v[126:127], 2, v[122:123]
	s_waitcnt vmcnt(0) lgkmcnt(0)
	v_pk_fma_f32 v[104:105], v[104:105], v[108:109], v[112:113]
	v_pk_fma_f32 v[102:103], v[102:103], v[106:107], v[110:111]
	global_store_dwordx4 v[124:125], v[102:105], off offset:512
	global_load_dwordx4 v[102:105], v[114:115], off
	s_nop 0
	global_load_dwordx4 v[106:109], v[136:137], off offset:576
	s_waitcnt vmcnt(0) lgkmcnt(0)
	v_pk_fma_f32 v[100:101], v[100:101], v[104:105], v[108:109]
	v_pk_fma_f32 v[98:99], v[98:99], v[102:103], v[106:107]
	global_store_dwordx4 v[124:125], v[98:101], off offset:576
.LBB0_5522:
	s_or_b64 exec, exec, s[6:7]
	s_nop 0
	v_or_b32_e32 v98, 32, v134
	s_movk_i32 s4, 0x4080
	v_cmp_gt_i32_e32 vcc, s4, v98
	s_and_saveexec_b64 s[6:7], vcc
	s_cbranch_execz .LBB0_5524
	s_movk_i32 s12, 0x4000
	v_readlane_b32 s14, v228, 17
	v_add_u32_e32 v99, 0xffffc022, v134
	v_mov_b32_e32 v100, s3
	v_cmp_gt_i32_e32 vcc, s12, v98
	v_readlane_b32 s15, v228, 18
	s_mov_b32 s12, 0x9000
	v_cndmask_b32_e32 v99, v99, v100, vcc
	v_mov_b64_e32 v[100:101], s[14:15]
	v_mad_i64_i32 v[100:101], s[12:13], v99, s12, v[100:101]
	v_ashrrev_i32_e32 v99, 31, v98
	v_lshlrev_b64 v[98:99], 12, v[98:99]
	v_add_u32_e32 v110, 0xffffc020, v134
	v_mov_b32_e32 v111, 0
	v_lshl_add_u64 v[108:109], s[10:11], 0, v[98:99]
	v_lshlrev_b64 v[98:99], 12, v[110:111]
	s_mov_b64 s[12:13], 0x5000
	v_lshl_add_u64 v[98:99], s[8:9], 0, v[98:99]
	v_mov_b32_e32 v131, v111
	v_lshl_add_u64 v[106:107], v[100:101], 0, s[12:13]
	v_cndmask_b32_e32 v103, v99, v109, vcc
	v_cndmask_b32_e32 v102, v98, v108, vcc
	v_lshlrev_b64 v[112:113], 2, v[130:131]
	v_lshl_add_u64 v[98:99], v[106:107], 0, v[112:113]
	v_lshl_add_u64 v[114:115], v[102:103], 0, v[112:113]
	global_load_dwordx4 v[98:101], v[98:99], off
	v_mov_b32_e32 v133, v111
	global_load_dwordx4 v[102:105], v[114:115], off
	v_lshl_add_u64 v[108:109], v[108:109], 0, v[112:113]
	v_lshl_add_u64 v[112:113], v[132:133], 2, v[106:107]
	v_or_b32_e32 v110, 0x80, v130
	s_waitcnt vmcnt(0) lgkmcnt(0)
	v_pk_fma_f32 v[96:97], v[96:97], v[100:101], v[104:105]
	v_pk_fma_f32 v[94:95], v[94:95], v[98:99], v[102:103]
	global_store_dwordx4 v[108:109], v[94:97], off
	global_load_dwordx4 v[94:97], v[112:113], off
	s_nop 0
	global_load_dwordx4 v[98:101], v[114:115], off offset:64
	v_lshl_add_u64 v[102:103], v[110:111], 2, v[106:107]
	v_or_b32_e32 v110, 0x90, v130
	s_waitcnt vmcnt(0) lgkmcnt(0)
	v_pk_fma_f32 v[92:93], v[92:93], v[96:97], v[100:101]
	v_pk_fma_f32 v[90:91], v[90:91], v[94:95], v[98:99]
	global_store_dwordx4 v[108:109], v[90:93], off offset:64
	global_load_dwordx4 v[90:93], v[102:103], off
	s_nop 0
	global_load_dwordx4 v[94:97], v[114:115], off offset:512
	v_lshl_add_u64 v[98:99], v[110:111], 2, v[106:107]
	s_waitcnt vmcnt(0) lgkmcnt(0)
	v_pk_fma_f32 v[88:89], v[88:89], v[92:93], v[96:97]
	v_pk_fma_f32 v[86:87], v[86:87], v[90:91], v[94:95]
	global_store_dwordx4 v[108:109], v[86:89], off offset:512
	global_load_dwordx4 v[86:89], v[98:99], off
	s_nop 0
	global_load_dwordx4 v[90:93], v[114:115], off offset:576
	s_waitcnt vmcnt(0) lgkmcnt(0)
	v_pk_fma_f32 v[84:85], v[84:85], v[88:89], v[92:93]
	v_pk_fma_f32 v[82:83], v[82:83], v[86:87], v[90:91]
	global_store_dwordx4 v[108:109], v[82:85], off offset:576
.LBB0_5524:
	s_or_b64 exec, exec, s[6:7]
	s_nop 0
	v_or_b32_e32 v82, 48, v134
	v_cmp_gt_i32_e32 vcc, s4, v82
	s_and_saveexec_b64 s[6:7], vcc
	s_cbranch_execz .LBB0_5526
	s_movk_i32 s4, 0x4000
	v_readlane_b32 s12, v228, 17
	v_add_u32_e32 v83, 0xffffc032, v134
	v_mov_b32_e32 v84, s3
	v_cmp_gt_i32_e32 vcc, s4, v82
	v_readlane_b32 s13, v228, 18
	s_mov_b32 s3, 0x9000
	v_cndmask_b32_e32 v83, v83, v84, vcc
	v_mov_b64_e32 v[84:85], s[12:13]
	v_mad_i64_i32 v[84:85], s[12:13], v83, s3, v[84:85]
	v_ashrrev_i32_e32 v83, 31, v82
	v_lshlrev_b64 v[82:83], 12, v[82:83]
	v_add_u32_e32 v94, 0xffffc030, v134
	v_mov_b32_e32 v95, 0
	v_lshl_add_u64 v[92:93], s[10:11], 0, v[82:83]
	v_lshlrev_b64 v[82:83], 12, v[94:95]
	s_mov_b64 s[12:13], 0x5000
	v_lshl_add_u64 v[82:83], s[8:9], 0, v[82:83]
	v_mov_b32_e32 v131, v95
	v_lshl_add_u64 v[90:91], v[84:85], 0, s[12:13]
	v_cndmask_b32_e32 v87, v83, v93, vcc
	v_cndmask_b32_e32 v86, v82, v92, vcc
	v_lshlrev_b64 v[96:97], 2, v[130:131]
	v_lshl_add_u64 v[82:83], v[90:91], 0, v[96:97]
	v_lshl_add_u64 v[98:99], v[86:87], 0, v[96:97]
	global_load_dwordx4 v[82:85], v[82:83], off
	v_mov_b32_e32 v133, v95
	global_load_dwordx4 v[86:89], v[98:99], off
	v_lshl_add_u64 v[92:93], v[92:93], 0, v[96:97]
	v_lshl_add_u64 v[96:97], v[132:133], 2, v[90:91]
	v_or_b32_e32 v94, 0x80, v130
	s_waitcnt vmcnt(0) lgkmcnt(0)
	v_pk_fma_f32 v[80:81], v[80:81], v[84:85], v[88:89]
	v_pk_fma_f32 v[78:79], v[78:79], v[82:83], v[86:87]
	global_store_dwordx4 v[92:93], v[78:81], off
	global_load_dwordx4 v[78:81], v[96:97], off
	s_nop 0
	global_load_dwordx4 v[82:85], v[98:99], off offset:64
	v_lshl_add_u64 v[86:87], v[94:95], 2, v[90:91]
	v_or_b32_e32 v94, 0x90, v130
	s_waitcnt vmcnt(0) lgkmcnt(0)
	v_pk_fma_f32 v[76:77], v[76:77], v[80:81], v[84:85]
	v_pk_fma_f32 v[74:75], v[74:75], v[78:79], v[82:83]
	global_store_dwordx4 v[92:93], v[74:77], off offset:64
	global_load_dwordx4 v[74:77], v[86:87], off
	s_nop 0
	global_load_dwordx4 v[78:81], v[98:99], off offset:512
	v_lshl_add_u64 v[82:83], v[94:95], 2, v[90:91]
	s_waitcnt vmcnt(0) lgkmcnt(0)
	v_pk_fma_f32 v[72:73], v[72:73], v[76:77], v[80:81]
	v_pk_fma_f32 v[70:71], v[70:71], v[74:75], v[78:79]
	global_store_dwordx4 v[92:93], v[70:73], off offset:512
	global_load_dwordx4 v[70:73], v[82:83], off
	s_nop 0
	global_load_dwordx4 v[74:77], v[98:99], off offset:576
	s_waitcnt vmcnt(0) lgkmcnt(0)
	v_pk_fma_f32 v[68:69], v[68:69], v[72:73], v[76:77]
	v_pk_fma_f32 v[66:67], v[66:67], v[70:71], v[74:75]
	global_store_dwordx4 v[92:93], v[66:69], off offset:576
.LBB0_5526:
	s_or_b64 exec, exec, s[6:7]
	s_addk_i32 s2, 0x4080
	s_movk_i32 s3, 0x4080
	v_or_b32_e32 v66, s2, v1
	s_ashr_i32 s2, s2, 13
	v_cmp_gt_i32_e32 vcc, s3, v66
	s_and_saveexec_b64 s[6:7], vcc
	s_cbranch_execz .LBB0_5528
	s_movk_i32 s4, 0x4000
	v_readlane_b32 s12, v228, 17
	v_add_u32_e32 v1, 0xffffc002, v66
	v_mov_b32_e32 v67, s2
	v_cmp_gt_i32_e32 vcc, s4, v66
	v_readlane_b32 s13, v228, 18
	s_mov_b32 s4, 0x9000
	v_cndmask_b32_e32 v1, v1, v67, vcc
	v_mov_b64_e32 v[68:69], s[12:13]
	v_mad_i64_i32 v[68:69], s[12:13], v1, s4, v[68:69]
	s_mov_b64 s[12:13], 0x5000
	v_ashrrev_i32_e32 v67, 31, v66
	v_lshl_add_u64 v[76:77], v[68:69], 0, s[12:13]
	v_lshlrev_b64 v[68:69], 12, v[66:67]
	v_add_u32_e32 v80, 0xffffc000, v66
	v_mov_b32_e32 v81, 0
	v_lshl_add_u64 v[78:79], s[10:11], 0, v[68:69]
	v_lshlrev_b64 v[68:69], 12, v[80:81]
	v_lshl_add_u64 v[68:69], s[8:9], 0, v[68:69]
	v_mov_b32_e32 v131, v81
	v_cndmask_b32_e32 v73, v69, v79, vcc
	v_cndmask_b32_e32 v72, v68, v78, vcc
	v_lshlrev_b64 v[82:83], 2, v[130:131]
	v_lshl_add_u64 v[68:69], v[76:77], 0, v[82:83]
	v_lshl_add_u64 v[84:85], v[72:73], 0, v[82:83]
	global_load_dwordx4 v[68:71], v[68:69], off
	v_mov_b32_e32 v133, v81
	global_load_dwordx4 v[72:75], v[84:85], off
	v_lshl_add_u64 v[78:79], v[78:79], 0, v[82:83]
	v_lshl_add_u64 v[82:83], v[132:133], 2, v[76:77]
	v_or_b32_e32 v80, 0x80, v130
	s_waitcnt vmcnt(0) lgkmcnt(0)
	v_pk_fma_f32 v[64:65], v[64:65], v[70:71], v[74:75]
	v_pk_fma_f32 v[62:63], v[62:63], v[68:69], v[72:73]
	global_store_dwordx4 v[78:79], v[62:65], off
	global_load_dwordx4 v[62:65], v[82:83], off
	s_nop 0
	global_load_dwordx4 v[68:71], v[84:85], off offset:64
	v_lshl_add_u64 v[72:73], v[80:81], 2, v[76:77]
	v_or_b32_e32 v80, 0x90, v130
	s_waitcnt vmcnt(0) lgkmcnt(0)
	v_pk_fma_f32 v[60:61], v[60:61], v[64:65], v[70:71]
	v_pk_fma_f32 v[58:59], v[58:59], v[62:63], v[68:69]
	global_store_dwordx4 v[78:79], v[58:61], off offset:64
	global_load_dwordx4 v[58:61], v[72:73], off
	s_nop 0
	global_load_dwordx4 v[62:65], v[84:85], off offset:512
	v_lshl_add_u64 v[68:69], v[80:81], 2, v[76:77]
	s_waitcnt vmcnt(0) lgkmcnt(0)
	v_pk_fma_f32 v[56:57], v[56:57], v[60:61], v[64:65]
	v_pk_fma_f32 v[54:55], v[54:55], v[58:59], v[62:63]
	global_store_dwordx4 v[78:79], v[54:57], off offset:512
	global_load_dwordx4 v[54:57], v[68:69], off
	s_nop 0
	global_load_dwordx4 v[58:61], v[84:85], off offset:576
	s_waitcnt vmcnt(0) lgkmcnt(0)
	v_pk_fma_f32 v[52:53], v[52:53], v[56:57], v[60:61]
	v_pk_fma_f32 v[50:51], v[50:51], v[54:55], v[58:59]
	global_store_dwordx4 v[78:79], v[50:53], off offset:576
.LBB0_5528:
	s_or_b64 exec, exec, s[6:7]
	s_nop 0
	v_or_b32_e32 v50, 16, v66
	v_cmp_gt_i32_e32 vcc, s3, v50
	s_and_saveexec_b64 s[6:7], vcc
	s_cbranch_execz .LBB0_5530
	s_movk_i32 s3, 0x4000
	v_add_u32_e32 v1, 0xffffc012, v66
	v_mov_b32_e32 v51, s2
	v_cmp_gt_i32_e32 vcc, s3, v50
	v_readlane_b32 s12, v228, 17
	v_readlane_b32 s13, v228, 18
	v_cndmask_b32_e32 v1, v1, v51, vcc
	v_ashrrev_i32_e32 v51, 31, v50
	s_mov_b32 s3, 0x9000
	v_mov_b64_e32 v[52:53], s[12:13]
	v_lshlrev_b64 v[50:51], 12, v[50:51]
	v_add_u32_e32 v62, 0xffffc010, v66
	v_mov_b32_e32 v63, 0
	v_mad_i64_i32 v[52:53], s[12:13], v1, s3, v[52:53]
	v_lshl_add_u64 v[60:61], s[10:11], 0, v[50:51]
	v_lshlrev_b64 v[50:51], 12, v[62:63]
	s_mov_b64 s[12:13], 0x5000
	v_lshl_add_u64 v[50:51], s[8:9], 0, v[50:51]
	v_mov_b32_e32 v131, v63
	v_lshl_add_u64 v[58:59], v[52:53], 0, s[12:13]
	v_cndmask_b32_e32 v55, v51, v61, vcc
	v_cndmask_b32_e32 v54, v50, v60, vcc
	v_lshlrev_b64 v[64:65], 2, v[130:131]
	v_lshl_add_u64 v[50:51], v[58:59], 0, v[64:65]
	v_lshl_add_u64 v[68:69], v[54:55], 0, v[64:65]
	global_load_dwordx4 v[50:53], v[50:51], off
	v_mov_b32_e32 v133, v63
	global_load_dwordx4 v[54:57], v[68:69], off
	v_lshl_add_u64 v[60:61], v[60:61], 0, v[64:65]
	v_lshl_add_u64 v[64:65], v[132:133], 2, v[58:59]
	v_or_b32_e32 v62, 0x80, v130
	s_waitcnt vmcnt(0) lgkmcnt(0)
	v_pk_fma_f32 v[48:49], v[48:49], v[52:53], v[56:57]
	v_pk_fma_f32 v[46:47], v[46:47], v[50:51], v[54:55]
	global_store_dwordx4 v[60:61], v[46:49], off
	global_load_dwordx4 v[46:49], v[64:65], off
	s_nop 0
	global_load_dwordx4 v[50:53], v[68:69], off offset:64
	v_lshl_add_u64 v[54:55], v[62:63], 2, v[58:59]
	v_or_b32_e32 v62, 0x90, v130
	s_waitcnt vmcnt(0) lgkmcnt(0)
	v_pk_fma_f32 v[44:45], v[44:45], v[48:49], v[52:53]
	v_pk_fma_f32 v[42:43], v[42:43], v[46:47], v[50:51]
	global_store_dwordx4 v[60:61], v[42:45], off offset:64
	global_load_dwordx4 v[42:45], v[54:55], off
	s_nop 0
	global_load_dwordx4 v[46:49], v[68:69], off offset:512
	v_lshl_add_u64 v[50:51], v[62:63], 2, v[58:59]
	s_waitcnt vmcnt(0) lgkmcnt(0)
	v_pk_fma_f32 v[40:41], v[40:41], v[44:45], v[48:49]
	v_pk_fma_f32 v[38:39], v[38:39], v[42:43], v[46:47]
	global_store_dwordx4 v[60:61], v[38:41], off offset:512
	global_load_dwordx4 v[38:41], v[50:51], off
	s_nop 0
	global_load_dwordx4 v[42:45], v[68:69], off offset:576
	s_waitcnt vmcnt(0) lgkmcnt(0)
	v_pk_fma_f32 v[36:37], v[36:37], v[40:41], v[44:45]
	v_pk_fma_f32 v[34:35], v[34:35], v[38:39], v[42:43]
	global_store_dwordx4 v[60:61], v[34:37], off offset:576
.LBB0_5530:
	s_or_b64 exec, exec, s[6:7]
	s_nop 0
	v_or_b32_e32 v34, 32, v66
	s_movk_i32 s3, 0x4080
	v_cmp_gt_i32_e32 vcc, s3, v34
	s_and_saveexec_b64 s[6:7], vcc
	s_cbranch_execz .LBB0_5532
	s_movk_i32 s4, 0x4000
	v_add_u32_e32 v1, 0xffffc022, v66
	v_mov_b32_e32 v35, s2
	v_cmp_gt_i32_e32 vcc, s4, v34
	v_readlane_b32 s12, v228, 17
	v_readlane_b32 s13, v228, 18
	v_cndmask_b32_e32 v1, v1, v35, vcc
	v_ashrrev_i32_e32 v35, 31, v34
	s_mov_b32 s4, 0x9000
	v_mov_b64_e32 v[36:37], s[12:13]
	v_lshlrev_b64 v[34:35], 12, v[34:35]
	v_add_u32_e32 v46, 0xffffc020, v66
	v_mov_b32_e32 v47, 0
	v_mad_i64_i32 v[36:37], s[12:13], v1, s4, v[36:37]
	v_lshl_add_u64 v[44:45], s[10:11], 0, v[34:35]
	v_lshlrev_b64 v[34:35], 12, v[46:47]
	s_mov_b64 s[12:13], 0x5000
	v_lshl_add_u64 v[34:35], s[8:9], 0, v[34:35]
	v_mov_b32_e32 v131, v47
	v_lshl_add_u64 v[42:43], v[36:37], 0, s[12:13]
	v_cndmask_b32_e32 v39, v35, v45, vcc
	v_cndmask_b32_e32 v38, v34, v44, vcc
	v_lshlrev_b64 v[48:49], 2, v[130:131]
	v_lshl_add_u64 v[34:35], v[42:43], 0, v[48:49]
	v_lshl_add_u64 v[50:51], v[38:39], 0, v[48:49]
	global_load_dwordx4 v[34:37], v[34:35], off
	v_mov_b32_e32 v133, v47
	global_load_dwordx4 v[38:41], v[50:51], off
	v_lshl_add_u64 v[44:45], v[44:45], 0, v[48:49]
	v_lshl_add_u64 v[48:49], v[132:133], 2, v[42:43]
	v_or_b32_e32 v46, 0x80, v130
	s_waitcnt vmcnt(0) lgkmcnt(0)
	v_pk_fma_f32 v[32:33], v[32:33], v[36:37], v[40:41]
	v_pk_fma_f32 v[30:31], v[30:31], v[34:35], v[38:39]
	global_store_dwordx4 v[44:45], v[30:33], off
	global_load_dwordx4 v[30:33], v[48:49], off
	s_nop 0
	global_load_dwordx4 v[34:37], v[50:51], off offset:64
	v_lshl_add_u64 v[38:39], v[46:47], 2, v[42:43]
	v_or_b32_e32 v46, 0x90, v130
	s_waitcnt vmcnt(0) lgkmcnt(0)
	v_pk_fma_f32 v[28:29], v[28:29], v[32:33], v[36:37]
	v_pk_fma_f32 v[26:27], v[26:27], v[30:31], v[34:35]
	global_store_dwordx4 v[44:45], v[26:29], off offset:64
	global_load_dwordx4 v[26:29], v[38:39], off
	s_nop 0
	global_load_dwordx4 v[30:33], v[50:51], off offset:512
	v_lshl_add_u64 v[34:35], v[46:47], 2, v[42:43]
	s_waitcnt vmcnt(0) lgkmcnt(0)
	v_pk_fma_f32 v[24:25], v[24:25], v[28:29], v[32:33]
	v_pk_fma_f32 v[22:23], v[22:23], v[26:27], v[30:31]
	global_store_dwordx4 v[44:45], v[22:25], off offset:512
	global_load_dwordx4 v[22:25], v[34:35], off
	s_nop 0
	global_load_dwordx4 v[26:29], v[50:51], off offset:576
	s_waitcnt vmcnt(0) lgkmcnt(0)
	v_pk_fma_f32 v[20:21], v[20:21], v[24:25], v[28:29]
	v_pk_fma_f32 v[18:19], v[18:19], v[22:23], v[26:27]
	global_store_dwordx4 v[44:45], v[18:21], off offset:576
.LBB0_5532:
	s_or_b64 exec, exec, s[6:7]
	s_nop 0
	v_or_b32_e32 v18, 48, v66
	v_cmp_gt_i32_e32 vcc, s3, v18
	s_and_saveexec_b64 s[6:7], vcc
	s_cbranch_execz .LBB0_5534
	s_movk_i32 s3, 0x4000
	v_add_u32_e32 v1, 0xffffc032, v66
	v_mov_b32_e32 v19, s2
	v_cmp_gt_i32_e32 vcc, s3, v18
	v_readlane_b32 s12, v228, 17
	v_readlane_b32 s13, v228, 18
	v_cndmask_b32_e32 v1, v1, v19, vcc
	v_ashrrev_i32_e32 v19, 31, v18
	s_mov_b32 s2, 0x9000
	v_mov_b64_e32 v[20:21], s[12:13]
	v_lshlrev_b64 v[18:19], 12, v[18:19]
	v_add_u32_e32 v30, 0xffffc030, v66
	v_mov_b32_e32 v31, 0
	v_mad_i64_i32 v[20:21], s[2:3], v1, s2, v[20:21]
	v_lshl_add_u64 v[28:29], s[10:11], 0, v[18:19]
	v_lshlrev_b64 v[18:19], 12, v[30:31]
	s_mov_b64 s[2:3], 0x5000
	v_lshl_add_u64 v[18:19], s[8:9], 0, v[18:19]
	v_mov_b32_e32 v131, v31
	v_lshl_add_u64 v[26:27], v[20:21], 0, s[2:3]
	v_cndmask_b32_e32 v23, v19, v29, vcc
	v_cndmask_b32_e32 v22, v18, v28, vcc
	v_lshlrev_b64 v[32:33], 2, v[130:131]
	v_lshl_add_u64 v[18:19], v[26:27], 0, v[32:33]
	v_lshl_add_u64 v[34:35], v[22:23], 0, v[32:33]
	global_load_dwordx4 v[18:21], v[18:19], off
	v_mov_b32_e32 v133, v31
	global_load_dwordx4 v[22:25], v[34:35], off
	v_lshl_add_u64 v[28:29], v[28:29], 0, v[32:33]
	v_lshl_add_u64 v[32:33], v[132:133], 2, v[26:27]
	v_or_b32_e32 v30, 0x80, v130
	s_waitcnt vmcnt(0) lgkmcnt(0)
	v_pk_fma_f32 v[16:17], v[16:17], v[20:21], v[24:25]
	v_pk_fma_f32 v[14:15], v[14:15], v[18:19], v[22:23]
	global_store_dwordx4 v[28:29], v[14:17], off
	global_load_dwordx4 v[14:17], v[32:33], off
	s_nop 0
	global_load_dwordx4 v[18:21], v[34:35], off offset:64
	v_lshl_add_u64 v[22:23], v[30:31], 2, v[26:27]
	v_or_b32_e32 v30, 0x90, v130
	s_waitcnt vmcnt(0) lgkmcnt(0)
	v_pk_fma_f32 v[12:13], v[12:13], v[16:17], v[20:21]
	v_pk_fma_f32 v[10:11], v[10:11], v[14:15], v[18:19]
	global_store_dwordx4 v[28:29], v[10:13], off offset:64
	global_load_dwordx4 v[10:13], v[22:23], off
	s_nop 0
	global_load_dwordx4 v[14:17], v[34:35], off offset:512
	v_lshl_add_u64 v[18:19], v[30:31], 2, v[26:27]
	s_waitcnt vmcnt(0) lgkmcnt(0)
	v_pk_fma_f32 v[8:9], v[8:9], v[12:13], v[16:17]
	v_pk_fma_f32 v[6:7], v[6:7], v[10:11], v[14:15]
	global_store_dwordx4 v[28:29], v[6:9], off offset:512
	global_load_dwordx4 v[6:9], v[18:19], off
	s_nop 0
	global_load_dwordx4 v[10:13], v[34:35], off offset:576
	s_waitcnt vmcnt(0) lgkmcnt(0)
	v_pk_fma_f32 v[4:5], v[4:5], v[8:9], v[12:13]
	v_pk_fma_f32 v[2:3], v[2:3], v[6:7], v[10:11]
	global_store_dwordx4 v[28:29], v[2:5], off offset:576

.LBB0_5542:
	s_or_b64 exec, exec, s[6:7]
	v_mov_b32_e32 v1, v0
	v_mov_b64_e32 v[2:3], s[0:1]
	s_barrier
	global_load_dwordx2 v[2:3], v[2:3], off offset:88 sc0 sc1
	s_waitcnt vmcnt(0)
	v_readfirstlane_b32 s2, v1
	s_ashr_i32 s2, s2, 4
	s_and_b32 s3, s2, -4
	s_cmp_gt_i32 s3, 31
	s_cbranch_scc1 .LBB0_5545
	v_and_b32_e32 v21, 63, v1
	v_mov_b32_e32 v91, 0
	v_lshlrev_b32_e32 v90, 4, v21
	s_waitcnt lgkmcnt(0)
	v_lshl_add_u64 v[2:3], v[2:3], 0, v[90:91]
	s_movk_i32 s2, 0x5000
	v_add_co_u32_e32 v18, vcc, s2, v2
	v_and_b32_e32 v1, 64, v166
	s_nop 0
	v_addc_co_u32_e32 v19, vcc, 0, v3, vcc
	global_load_dwordx4 v[2:5], v[18:19], off
	global_load_dwordx4 v[6:9], v[18:19], off offset:1024
	global_load_dwordx4 v[10:13], v[18:19], off offset:2048
	global_load_dwordx4 v[14:17], v[18:19], off offset:3072
	v_add_u32_e32 v18, 64, v1
	v_xor_b32_e32 v1, 1, v166
	v_cmp_lt_i32_e32 vcc, v1, v18
	v_xor_b32_e32 v19, 2, v166
	s_lshl_b32 s4, s40, 5
	v_cndmask_b32_e32 v1, v166, v1, vcc
	v_cmp_lt_i32_e32 vcc, v19, v18
	s_add_i32 s3, s4, s3
	s_add_i32 s2, s4, 0x20a0
	v_cndmask_b32_e32 v19, v166, v19, vcc
	v_lshlrev_b32_e32 v167, 2, v19
	v_xor_b32_e32 v19, 4, v166
	v_cmp_lt_i32_e32 vcc, v19, v18
	s_add_i32 s12, s3, 0x2080
	s_add_u32 s3, s68, 0x5800000
	v_cndmask_b32_e32 v19, v166, v19, vcc
	v_lshlrev_b32_e32 v168, 2, v19
	v_xor_b32_e32 v19, 8, v166
	v_cmp_lt_i32_e32 vcc, v19, v18
	s_addc_u32 s4, s69, 0
	s_ashr_i32 s13, s12, 31
	v_cndmask_b32_e32 v19, v166, v19, vcc
	v_lshlrev_b32_e32 v169, 2, v19
	v_xor_b32_e32 v19, 16, v166
	v_cmp_lt_i32_e32 vcc, v19, v18
	s_lshl_b64 s[6:7], s[12:13], 11
	v_lshl_or_b32 v92, v21, 3, s6
	v_cndmask_b32_e32 v19, v166, v19, vcc
	v_lshlrev_b32_e32 v170, 2, v19
	v_xor_b32_e32 v19, 32, v166
	v_cmp_lt_i32_e32 vcc, v19, v18
	v_mov_b32_e32 v93, s7
	s_lshl_b64 s[6:7], s[12:13], 12
	v_cndmask_b32_e32 v18, v166, v19, vcc
	v_lshlrev_b32_e32 v171, 2, v18
	v_lshlrev_b32_e32 v18, 2, v21
	v_or_b32_e32 v20, 0x100, v18
	v_or_b32_e32 v22, 0x200, v18
	v_or_b32_e32 v24, 0x300, v18
	v_lshlrev_b32_e32 v1, 2, v1
	v_or_b32_e32 v94, s6, v90
	v_mov_b32_e32 v95, s7
	v_mov_b32_e32 v172, 0x358637bd
	s_mov_b32 s13, 0xf800000
	v_mov_b32_e32 v173, 0x260
	v_lshlrev_b32_e32 v90, 2, v18
	s_movk_i32 s22, 0x7fff
	s_mov_b32 s23, 0xffff0000
	s_mov_b32 s24, 0xba00000
	v_lshlrev_b32_e32 v96, 2, v20
	v_lshlrev_b32_e32 v98, 2, v22
	v_mov_b32_e32 v99, v91
	v_lshlrev_b32_e32 v100, 2, v24
	v_mov_b32_e32 v101, v91
	s_mov_b32 s25, 0xba01000
	s_mov_b64 s[14:15], 0x10000
	s_mov_b64 s[16:17], 0x20000
	v_mov_b32_e32 v97, v91
.LBB0_5544:
	v_lshl_add_u64 v[18:19], s[68:69], 0, v[94:95]
	v_lshl_add_u64 v[22:23], s[68:69], 0, v[92:93]
	v_add_co_u32_e32 v20, vcc, 0x7800000, v18
	v_add_co_u32_e64 v102, s[6:7], s24, v22
	s_nop 0
	v_addc_co_u32_e32 v21, vcc, 0, v19, vcc
	v_addc_co_u32_e64 v103, s[6:7], 0, v23, s[6:7]
	v_add_co_u32_e64 v104, s[6:7], s25, v22
	v_add_co_u32_e32 v22, vcc, 0x7801000, v18
	s_nop 0
	v_addc_co_u32_e64 v105, s[6:7], 0, v23, s[6:7]
	global_load_dwordx4 v[78:81], v[20:21], off
	global_load_dwordx4 v[74:77], v[20:21], off offset:1024
	global_load_dwordx4 v[70:73], v[20:21], off offset:2048
	global_load_dwordx4 v[66:69], v[20:21], off offset:3072
	v_addc_co_u32_e32 v23, vcc, 0, v19, vcc
	v_add_co_u32_e32 v20, vcc, 0x7802000, v18
	global_load_dwordx4 v[62:65], v[22:23], off
	global_load_dwordx4 v[58:61], v[22:23], off offset:1024
	global_load_dwordx4 v[54:57], v[22:23], off offset:2048
	global_load_dwordx4 v[50:53], v[22:23], off offset:3072
	v_addc_co_u32_e32 v21, vcc, 0, v19, vcc
	v_add_co_u32_e32 v82, vcc, 0x7803000, v18
	global_load_dwordx4 v[46:49], v[20:21], off
	global_load_dwordx4 v[42:45], v[20:21], off offset:1024
	global_load_dwordx4 v[38:41], v[20:21], off offset:2048
	global_load_dwordx4 v[34:37], v[20:21], off offset:3072
	v_addc_co_u32_e32 v83, vcc, 0, v19, vcc
	global_load_dwordx4 v[30:33], v[82:83], off
	global_load_dwordx4 v[26:29], v[82:83], off offset:1024
	global_load_dwordx4 v[22:25], v[82:83], off offset:2048
	global_load_dwordx4 v[18:21], v[82:83], off offset:3072
	s_ashr_i32 s8, s12, 13
	s_add_i32 s9, s12, 0xffffc002
	s_cmpk_lt_i32 s12, 0x4000
	s_cselect_b32 s6, s8, s9
	s_addk_i32 s6, 0x82
	s_mul_hi_i32 s7, s6, 0x9000
	s_mul_i32 s6, s6, 0x9000
	s_add_u32 s9, s3, s6
	s_addc_u32 s11, s4, s7
	s_add_u32 s6, s9, 0x6000
	s_addc_u32 s7, s11, 0
	s_add_u32 s10, s9, 0x7000
	s_addc_u32 s11, s11, 0
	v_lshl_add_u64 v[82:83], s[6:7], 0, v[90:91]
	v_lshl_add_u64 v[86:87], s[10:11], 0, v[90:91]
	global_load_dwordx4 v[82:85], v[82:83], off
	v_lshl_add_u64 v[148:149], s[6:7], 0, v[96:97]
	global_load_dwordx4 v[86:89], v[86:87], off
	v_lshl_add_u64 v[142:143], s[6:7], 0, v[98:99]
	v_lshl_add_u64 v[132:133], s[6:7], 0, v[100:101]
	s_add_i32 s6, s12, 0xffffc003
	s_cmpk_lt_i32 s12, 0x3fff
	s_cselect_b32 s6, s8, s6
	s_addk_i32 s6, 0x82
	s_mul_hi_i32 s7, s6, 0x9000
	s_mul_i32 s6, s6, 0x9000
	s_add_u32 s9, s3, s6
	v_lshl_add_u64 v[152:153], s[10:11], 0, v[96:97]
	v_lshl_add_u64 v[146:147], s[10:11], 0, v[98:99]
	v_lshl_add_u64 v[140:141], s[10:11], 0, v[100:101]
	s_addc_u32 s11, s4, s7
	s_add_u32 s6, s9, 0x6000
	s_addc_u32 s7, s11, 0
	s_add_u32 s10, s9, 0x7000
	v_lshl_add_u64 v[134:135], s[6:7], 0, v[90:91]
	v_lshl_add_u64 v[126:127], s[6:7], 0, v[96:97]
	v_lshl_add_u64 v[118:119], s[6:7], 0, v[98:99]
	v_lshl_add_u64 v[114:115], s[6:7], 0, v[100:101]
	s_addc_u32 s11, s11, 0
	s_add_i32 s6, s12, 0xffffc004
	s_cmpk_lt_i32 s12, 0x3ffe
	s_cselect_b32 s6, s8, s6
	s_addk_i32 s6, 0x82
	s_mul_hi_i32 s7, s6, 0x9000
	s_mul_i32 s6, s6, 0x9000
	s_add_u32 s6, s3, s6
	s_addc_u32 s7, s4, s7
	v_lshl_add_u64 v[136:137], s[10:11], 0, v[90:91]
	v_lshl_add_u64 v[130:131], s[10:11], 0, v[96:97]
	v_lshl_add_u64 v[122:123], s[10:11], 0, v[98:99]
	v_lshl_add_u64 v[116:117], s[10:11], 0, v[100:101]
	s_add_u32 s10, s6, 0x6000
	s_addc_u32 s11, s7, 0
	s_add_u32 s6, s6, 0x7000
	s_addc_u32 s7, s7, 0
	s_add_i32 s9, s12, 0xffffc005
	s_cmpk_lt_i32 s12, 0x3ffd
	v_lshl_add_u64 v[156:157], s[6:7], 0, v[90:91]
	v_lshl_add_u64 v[154:155], s[6:7], 0, v[96:97]
	v_lshl_add_u64 v[150:151], s[6:7], 0, v[98:99]
	v_lshl_add_u64 v[138:139], s[6:7], 0, v[100:101]
	s_cselect_b32 s6, s8, s9
	s_addk_i32 s6, 0x82
	s_waitcnt vmcnt(0) lgkmcnt(0)
	v_pk_mul_f32 v[158:159], v[80:81], v[80:81]
	v_pk_mul_f32 v[160:161], v[78:79], v[78:79]
	v_pk_mul_f32 v[162:163], v[76:77], v[76:77]
	v_pk_mul_f32 v[164:165], v[74:75], v[74:75]
	v_mul_f32_e32 v174, v71, v71
	v_mul_f32_e32 v176, v73, v73
	v_mul_f32_e32 v187, v68, v68
	v_mul_f32_e32 v189, v69, v69
	v_pk_mov_b32 v[178:179], v[160:161], v[158:159] op_sel:[1,0]
	v_mov_b32_e32 v161, v159
	v_pk_mov_b32 v[158:159], v[164:165], v[162:163] op_sel:[1,0]
	v_mov_b32_e32 v165, v163
	v_pk_fma_f32 v[162:163], v[70:71], v[70:71], v[174:175] op_sel_hi:[1,1,0]
	v_pk_fma_f32 v[174:175], v[72:73], v[72:73], v[176:177] op_sel_hi:[1,1,0]
	v_pk_mul_f32 v[176:177], v[64:65], v[64:65]
	v_pk_mul_f32 v[180:181], v[62:63], v[62:63]
	v_pk_mul_f32 v[182:183], v[60:61], v[60:61]
	v_pk_mul_f32 v[184:185], v[58:59], v[58:59]
	v_mul_f32_e32 v186, v55, v55
	v_mul_f32_e32 v188, v57, v57
	v_pk_add_f32 v[160:161], v[178:179], v[160:161]
	v_pk_add_f32 v[158:159], v[158:159], v[164:165]
	v_mov_b32_e32 v163, v187
	v_mov_b32_e32 v175, v189
	v_pk_mov_b32 v[164:165], v[180:181], v[176:177] op_sel:[1,0]
	v_mov_b32_e32 v181, v177
	v_pk_mov_b32 v[176:177], v[184:185], v[182:183] op_sel:[1,0]
	v_mov_b32_e32 v185, v183
	v_pk_fma_f32 v[178:179], v[54:55], v[54:55], v[186:187] op_sel_hi:[1,1,0]
	v_pk_fma_f32 v[182:183], v[56:57], v[56:57], v[188:189] op_sel_hi:[1,1,0]
	v_pk_mul_f32 v[186:187], v[48:49], v[48:49]
	v_pk_mul_f32 v[188:189], v[46:47], v[46:47]
	v_pk_mul_f32 v[190:191], v[44:45], v[44:45]
	v_pk_mul_f32 v[192:193], v[42:43], v[42:43]
	v_mul_f32_e32 v197, v66, v66
	v_mul_f32_e32 v203, v67, v67
	v_mul_f32_e32 v195, v52, v52
	v_mul_f32_e32 v202, v53, v53
	v_mul_f32_e32 v194, v39, v39
	v_mul_f32_e32 v196, v41, v41
	v_pk_add_f32 v[198:199], v[160:161], v[160:161] op_sel:[0,1] op_sel_hi:[1,0]
	v_pk_add_f32 v[200:201], v[158:159], v[158:159] op_sel:[0,1] op_sel_hi:[1,0]
	v_pk_add_f32 v[174:175], v[162:163], v[174:175]
	v_pk_add_f32 v[158:159], v[164:165], v[180:181]
	v_pk_add_f32 v[160:161], v[176:177], v[184:185]
	v_pk_mov_b32 v[162:163], v[188:189], v[186:187] op_sel:[1,0]
	v_mov_b32_e32 v189, v187
	v_pk_mov_b32 v[164:165], v[192:193], v[190:191] op_sel:[1,0]
	v_mov_b32_e32 v193, v191
	v_mul_f32_e32 v208, v50, v50
	v_mul_f32_e32 v209, v51, v51
	v_mul_f32_e32 v212, v36, v36
	v_mul_f32_e32 v213, v37, v37
	v_mov_b32_e32 v179, v195
	v_mov_b32_e32 v183, v202
	v_pk_fma_f32 v[176:177], v[38:39], v[38:39], v[194:195] op_sel_hi:[1,1,0]
	v_pk_fma_f32 v[180:181], v[40:41], v[40:41], v[196:197] op_sel_hi:[1,1,0]
	v_pk_mul_f32 v[184:185], v[32:33], v[32:33]
	v_pk_mul_f32 v[186:187], v[30:31], v[30:31]
	v_pk_mul_f32 v[190:191], v[28:29], v[28:29]
	v_pk_mul_f32 v[194:195], v[26:27], v[26:27]
	v_mov_b32_e32 v199, v197
	v_mov_b32_e32 v201, v203
	v_pk_add_f32 v[204:205], v[158:159], v[158:159] op_sel:[0,1] op_sel_hi:[1,0]
	v_pk_add_f32 v[206:207], v[160:161], v[160:161] op_sel:[0,1] op_sel_hi:[1,0]
	v_pk_add_f32 v[162:163], v[162:163], v[188:189]
	v_pk_add_f32 v[164:165], v[164:165], v[192:193]
	v_mul_f32_e32 v210, v34, v34
	v_mul_f32_e32 v211, v35, v35
	v_pk_add_f32 v[178:179], v[178:179], v[182:183]
	v_mov_b32_e32 v177, v212
	v_mov_b32_e32 v181, v213
	v_pk_mov_b32 v[182:183], v[186:187], v[184:185] op_sel:[1,0]
	v_mov_b32_e32 v187, v185
	v_pk_mov_b32 v[184:185], v[194:195], v[190:191] op_sel:[1,0]
	v_mov_b32_e32 v195, v191
	v_pk_add_f32 v[188:189], v[198:199], v[200:201]
	v_mov_b32_e32 v205, v208
	v_mov_b32_e32 v207, v209
	v_pk_add_f32 v[190:191], v[162:163], v[162:163] op_sel:[0,1] op_sel_hi:[1,0]
	v_pk_add_f32 v[192:193], v[164:165], v[164:165] op_sel:[0,1] op_sel_hi:[1,0]
	v_pk_add_f32 v[176:177], v[176:177], v[180:181]
	v_pk_add_f32 v[174:175], v[188:189], v[174:175]
	v_pk_add_f32 v[180:181], v[204:205], v[206:207]
	v_mov_b32_e32 v191, v210
	v_mov_b32_e32 v193, v211
	v_pk_add_f32 v[162:163], v[182:183], v[186:187]
	v_add_f32_e32 v182, v174, v175
	v_pk_add_f32 v[174:175], v[180:181], v[178:179]
	v_pk_add_f32 v[178:179], v[190:191], v[192:193]
	v_add_f32_e32 v180, v174, v175
	v_pk_add_f32 v[174:175], v[178:179], v[176:177]
	ds_bpermute_b32 v176, v1, v182
	v_add_f32_e32 v174, v174, v175
	ds_bpermute_b32 v175, v1, v180
	ds_bpermute_b32 v177, v1, v174
	s_mul_hi_i32 s7, s6, 0x9000
	s_waitcnt lgkmcnt(2)
	v_add_f32_e32 v176, v182, v176
	ds_bpermute_b32 v178, v167, v176
	s_waitcnt lgkmcnt(2)
	v_add_f32_e32 v175, v180, v175
	ds_bpermute_b32 v179, v167, v175
	s_waitcnt lgkmcnt(2)
	v_add_f32_e32 v174, v174, v177
	ds_bpermute_b32 v177, v167, v174
	s_waitcnt lgkmcnt(2)
	v_add_f32_e32 v176, v176, v178
	ds_bpermute_b32 v178, v168, v176
	s_waitcnt lgkmcnt(2)
	v_add_f32_e32 v175, v175, v179
	ds_bpermute_b32 v179, v168, v175
	s_waitcnt lgkmcnt(2)
	v_add_f32_e32 v174, v174, v177
	ds_bpermute_b32 v177, v168, v174
	s_waitcnt lgkmcnt(2)
	v_add_f32_e32 v176, v176, v178
	ds_bpermute_b32 v178, v169, v176
	s_waitcnt lgkmcnt(2)
	v_add_f32_e32 v175, v175, v179
	ds_bpermute_b32 v179, v169, v175
	s_waitcnt lgkmcnt(2)
	v_add_f32_e32 v174, v174, v177
	ds_bpermute_b32 v177, v169, v174
	s_waitcnt lgkmcnt(2)
	v_add_f32_e32 v176, v176, v178
	ds_bpermute_b32 v178, v170, v176
	s_waitcnt lgkmcnt(2)
	v_add_f32_e32 v175, v175, v179
	ds_bpermute_b32 v179, v170, v175
	s_waitcnt lgkmcnt(2)
	v_add_f32_e32 v174, v174, v177
	ds_bpermute_b32 v177, v170, v174
	s_waitcnt lgkmcnt(2)
	v_add_f32_e32 v176, v176, v178
	ds_bpermute_b32 v178, v171, v176
	s_waitcnt lgkmcnt(2)
	v_add_f32_e32 v175, v175, v179
	ds_bpermute_b32 v179, v171, v175
	s_mul_i32 s6, s6, 0x9000
	s_waitcnt lgkmcnt(2)
	v_add_f32_e32 v174, v174, v177
	s_add_u32 s6, s3, s6
	ds_bpermute_b32 v177, v171, v174
	s_addc_u32 s7, s4, s7
	s_waitcnt lgkmcnt(2)
	v_add_f32_e32 v176, v176, v178
	s_add_u32 s18, s6, 0x6000
	v_fmamk_f32 v176, v176, 0x3a800000, v172
	s_addc_u32 s19, s7, 0
	s_waitcnt lgkmcnt(1)
	v_add_f32_e32 v175, v175, v179
	v_mul_f32_e32 v178, 0x4f800000, v176
	v_cmp_gt_f32_e32 vcc, s13, v176
	s_add_u32 s20, s6, 0x7000
	v_fmamk_f32 v175, v175, 0x3a800000, v172
	v_cndmask_b32_e32 v176, v176, v178, vcc
	s_addc_u32 s21, s7, 0
	s_waitcnt lgkmcnt(0)
	v_add_f32_e32 v174, v174, v177
	v_mul_f32_e32 v177, 0x4f800000, v175
	v_cmp_gt_f32_e64 s[6:7], s13, v175
	v_sqrt_f32_e32 v178, v176
	v_fmamk_f32 v174, v174, 0x3a800000, v172
	v_cndmask_b32_e64 v175, v175, v177, s[6:7]
	v_mul_f32_e32 v177, 0x4f800000, v174
	v_cmp_gt_f32_e64 s[8:9], s13, v174
	v_sqrt_f32_e32 v179, v175
	v_add_u32_e32 v180, -1, v178
	v_cndmask_b32_e64 v174, v174, v177, s[8:9]
	v_sqrt_f32_e32 v177, v174
	v_add_u32_e32 v181, 1, v178
	v_fma_f32 v182, -v180, v178, v176
	v_lshl_add_u64 v[112:113], s[10:11], 0, v[90:91]
	v_lshl_add_u64 v[106:107], s[10:11], 0, v[96:97]
	v_lshl_add_u64 v[110:111], s[10:11], 0, v[98:99]
	v_lshl_add_u64 v[108:109], s[10:11], 0, v[100:101]
	v_pk_add_f32 v[164:165], v[184:185], v[194:195]
	v_fma_f32 v183, -v181, v178, v176
	v_add_u32_e32 v184, -1, v179
	v_cmp_ge_f32_e64 s[10:11], 0, v182
	v_add_u32_e32 v185, 1, v179
	v_fma_f32 v182, -v185, v179, v175
	v_cndmask_b32_e64 v178, v178, v180, s[10:11]
	v_fma_f32 v180, -v184, v179, v175
	v_cmp_lt_f32_e64 s[10:11], 0, v183
	v_add_u32_e32 v186, -1, v177
	v_add_u32_e32 v187, 1, v177
	v_cndmask_b32_e64 v178, v178, v181, s[10:11]
	v_cmp_ge_f32_e64 s[10:11], 0, v180
	v_fma_f32 v180, -v186, v177, v174
	v_fma_f32 v181, -v187, v177, v174
	v_cndmask_b32_e64 v179, v179, v184, s[10:11]
	v_cmp_lt_f32_e64 s[10:11], 0, v182
	v_mul_f32_e32 v182, 0x37800000, v178
	v_cndmask_b32_e32 v178, v178, v182, vcc
	v_cndmask_b32_e64 v179, v179, v185, s[10:11]
	v_cmp_ge_f32_e64 s[10:11], 0, v180
	v_cmp_class_f32_e32 vcc, v176, v173
	v_mul_f32_e32 v180, 0x37800000, v179
	v_cndmask_b32_e64 v177, v177, v186, s[10:11]
	v_cmp_lt_f32_e64 s[10:11], 0, v181
	v_cndmask_b32_e32 v176, v178, v176, vcc
	v_cndmask_b32_e64 v178, v179, v180, s[6:7]
	v_cndmask_b32_e64 v177, v177, v187, s[10:11]
	v_cmp_class_f32_e32 vcc, v175, v173
	v_mul_f32_e32 v179, 0x37800000, v177
	v_div_scale_f32 v180, s[6:7], v176, v176, 1.0
	v_cndmask_b32_e32 v175, v178, v175, vcc
	v_cndmask_b32_e64 v177, v177, v179, s[8:9]
	v_cmp_class_f32_e32 vcc, v174, v173
	v_rcp_f32_e32 v178, v180
	v_div_scale_f32 v179, s[8:9], v175, v175, 1.0
	v_cndmask_b32_e32 v177, v177, v174, vcc
	v_rcp_f32_e32 v183, v179
	v_div_scale_f32 v184, s[10:11], v177, v177, 1.0
	v_rcp_f32_e32 v186, v184
	v_fma_f32 v174, -v180, v178, 1.0
	v_div_scale_f32 v181, s[6:7], 1.0, v176, 1.0
	v_fmac_f32_e32 v178, v174, v178
	v_fma_f32 v174, -v179, v183, 1.0
	v_mul_f32_e32 v187, v181, v178
	v_div_scale_f32 v182, s[8:9], 1.0, v175, 1.0
	v_fmac_f32_e32 v183, v174, v183
	v_fma_f32 v174, -v184, v186, 1.0
	v_fma_f32 v188, -v180, v187, v181
	v_div_scale_f32 v185, s[10:11], 1.0, v177, 1.0
	v_mul_f32_e32 v189, v182, v183
	v_fmac_f32_e32 v186, v174, v186
	v_fmac_f32_e32 v187, v188, v178
	v_fma_f32 v174, -v179, v189, v182
	v_mul_f32_e32 v188, v185, v186
	v_fma_f32 v180, -v180, v187, v181
	s_mov_b64 vcc, s[6:7]
	v_fmac_f32_e32 v189, v174, v183
	v_fma_f32 v174, -v184, v188, v185
	v_div_fmas_f32 v178, v180, v178, v187
	v_fma_f32 v179, -v179, v189, v182
	v_fmac_f32_e32 v188, v174, v186
	v_div_fixup_f32 v174, v178, v176, 1.0
	s_mov_b64 vcc, s[8:9]
	v_div_fmas_f32 v176, v179, v183, v189
	v_fma_f32 v178, -v184, v188, v185
	v_pk_mul_f32 v[80:81], v[80:81], v[174:175] op_sel_hi:[1,0]
	v_pk_mul_f32 v[78:79], v[78:79], v[174:175] op_sel_hi:[1,0]
	s_mov_b64 vcc, s[10:11]
	v_pk_add_f32 v[88:89], v[88:89], 1.0 op_sel_hi:[1,0]
	v_pk_add_f32 v[86:87], v[86:87], 1.0 op_sel_hi:[1,0]
	v_pk_mul_f32 v[76:77], v[76:77], v[174:175] op_sel_hi:[1,0]
	v_pk_mul_f32 v[74:75], v[74:75], v[174:175] op_sel_hi:[1,0]
	v_pk_mul_f32 v[72:73], v[72:73], v[174:175] op_sel_hi:[1,0]
	v_pk_mul_f32 v[70:71], v[70:71], v[174:175] op_sel_hi:[1,0]
	v_pk_mul_f32 v[68:69], v[68:69], v[174:175] op_sel_hi:[1,0]
	v_pk_mul_f32 v[66:67], v[66:67], v[174:175] op_sel_hi:[1,0]
	v_div_fixup_f32 v174, v176, v175, 1.0
	v_div_fmas_f32 v176, v178, v186, v188
	v_pk_mul_f32 v[78:79], v[2:3], v[78:79]
	v_pk_mul_f32 v[80:81], v[4:5], v[80:81]
	v_pk_mul_f32 v[64:65], v[64:65], v[174:175] op_sel_hi:[1,0]
	v_pk_mul_f32 v[62:63], v[62:63], v[174:175] op_sel_hi:[1,0]
	v_pk_mul_f32 v[60:61], v[60:61], v[174:175] op_sel_hi:[1,0]
	v_pk_mul_f32 v[58:59], v[58:59], v[174:175] op_sel_hi:[1,0]
	v_pk_mul_f32 v[56:57], v[56:57], v[174:175] op_sel_hi:[1,0]
	v_pk_mul_f32 v[54:55], v[54:55], v[174:175] op_sel_hi:[1,0]
	v_pk_mul_f32 v[52:53], v[52:53], v[174:175] op_sel_hi:[1,0]
	v_pk_mul_f32 v[174:175], v[50:51], v[174:175] op_sel_hi:[1,0]
	v_div_fixup_f32 v50, v176, v177, 1.0
	v_pk_fma_f32 v[80:81], v[88:89], v[80:81], v[84:85]
	v_pk_fma_f32 v[78:79], v[86:87], v[78:79], v[82:83]
	v_pk_mul_f32 v[86:87], v[16:17], v[52:53]
	v_pk_mul_f32 v[48:49], v[48:49], v[50:51] op_sel_hi:[1,0]
	v_pk_mul_f32 v[46:47], v[46:47], v[50:51] op_sel_hi:[1,0]
	v_bfe_u32 v51, v78, 16, 1
	v_bfe_u32 v53, v80, 16, 1
	v_pk_mul_f32 v[82:83], v[10:11], v[54:55]
	v_pk_mul_f32 v[84:85], v[14:15], v[174:175]
	v_bfe_u32 v52, v79, 16, 1
	v_bfe_u32 v54, v81, 16, 1
	v_pk_mul_f32 v[88:89], v[2:3], v[46:47]
	v_pk_mul_f32 v[174:175], v[4:5], v[48:49]
	v_add3_u32 v46, v78, v51, s22
	v_add3_u32 v48, v80, v53, s22
	v_add3_u32 v47, v79, v52, s22
	v_add3_u32 v49, v81, v54, s22
	v_lshrrev_b32_e32 v46, 16, v46
	v_lshrrev_b32_e32 v48, 16, v48
	v_and_or_b32 v46, v47, s23, v46
	v_and_or_b32 v47, v49, s23, v48
	global_store_dwordx2 v[102:103], v[46:47], off
	global_load_dwordx4 v[46:49], v[152:153], off
	s_nop 0
	global_load_dwordx4 v[52:55], v[148:149], off
	v_pk_mul_f32 v[74:75], v[6:7], v[74:75]
	v_pk_mul_f32 v[76:77], v[8:9], v[76:77]
	v_pk_mul_f32 v[70:71], v[10:11], v[70:71]
	v_pk_mul_f32 v[72:73], v[12:13], v[72:73]
	v_pk_mul_f32 v[66:67], v[66:67], v[14:15]
	v_pk_mul_f32 v[68:69], v[68:69], v[16:17]
	v_pk_mul_f32 v[62:63], v[2:3], v[62:63]
	v_pk_mul_f32 v[64:65], v[4:5], v[64:65]
	v_pk_mul_f32 v[58:59], v[6:7], v[58:59]
	v_pk_mul_f32 v[60:61], v[8:9], v[60:61]
	v_pk_mul_f32 v[56:57], v[12:13], v[56:57]
	v_mul_f32_e32 v196, v23, v23
	v_mul_f32_e32 v202, v25, v25
	v_mul_f32_e32 v214, v18, v18
	v_mul_f32_e32 v215, v19, v19
	v_mul_f32_e32 v216, v20, v20
	v_mul_f32_e32 v217, v21, v21
	v_pk_fma_f32 v[158:159], v[22:23], v[22:23], v[196:197] op_sel_hi:[1,1,0]
	v_pk_fma_f32 v[160:161], v[24:25], v[24:25], v[202:203] op_sel_hi:[1,1,0]
	v_mov_b32_e32 v159, v216
	v_mov_b32_e32 v161, v217
	v_lshl_add_u64 v[144:145], s[20:21], 0, v[90:91]
	v_lshl_add_u64 v[128:129], s[18:19], 0, v[90:91]
	v_lshl_add_u64 v[124:125], s[20:21], 0, v[96:97]
	v_lshl_add_u64 v[120:121], s[18:19], 0, v[96:97]
	s_add_i32 s12, s12, 32
	v_lshl_add_u64 v[92:93], v[92:93], 0, s[14:15]
	v_lshl_add_u64 v[94:95], v[94:95], 0, s[16:17]
	s_cmp_lt_i32 s12, s2
	s_waitcnt vmcnt(0) lgkmcnt(0)
	v_pk_add_f32 v[48:49], v[48:49], 1.0 op_sel_hi:[1,0]
	v_pk_add_f32 v[46:47], v[46:47], 1.0 op_sel_hi:[1,0]
	v_pk_fma_f32 v[48:49], v[48:49], v[76:77], v[54:55]
	v_pk_fma_f32 v[46:47], v[46:47], v[74:75], v[52:53]
	v_bfe_u32 v53, v48, 16, 1
	v_bfe_u32 v51, v46, 16, 1
	v_bfe_u32 v52, v47, 16, 1
	v_bfe_u32 v54, v49, 16, 1
	v_add3_u32 v46, v46, v51, s22
	v_add3_u32 v48, v48, v53, s22
	v_add3_u32 v47, v47, v52, s22
	v_add3_u32 v49, v49, v54, s22
	v_lshrrev_b32_e32 v46, 16, v46
	v_lshrrev_b32_e32 v48, 16, v48
	v_and_or_b32 v46, v47, s23, v46
	v_and_or_b32 v47, v49, s23, v48
	global_store_dwordx2 v[102:103], v[46:47], off offset:512
	global_load_dwordx4 v[46:49], v[146:147], off
	s_nop 0
	global_load_dwordx4 v[52:55], v[142:143], off
	s_waitcnt vmcnt(0) lgkmcnt(0)
	v_pk_add_f32 v[48:49], v[48:49], 1.0 op_sel_hi:[1,0]
	v_pk_add_f32 v[46:47], v[46:47], 1.0 op_sel_hi:[1,0]
	v_pk_fma_f32 v[48:49], v[72:73], v[48:49], v[54:55]
	v_pk_fma_f32 v[46:47], v[70:71], v[46:47], v[52:53]
	v_bfe_u32 v53, v48, 16, 1
	v_bfe_u32 v51, v46, 16, 1
	v_bfe_u32 v52, v47, 16, 1
	v_bfe_u32 v54, v49, 16, 1
	v_add3_u32 v46, v46, v51, s22
	v_add3_u32 v48, v48, v53, s22
	v_add3_u32 v47, v47, v52, s22
	v_add3_u32 v49, v49, v54, s22
	v_lshrrev_b32_e32 v46, 16, v46
	v_lshrrev_b32_e32 v48, 16, v48
	v_and_or_b32 v46, v47, s23, v46
	v_and_or_b32 v47, v49, s23, v48
	global_store_dwordx2 v[102:103], v[46:47], off offset:1024
	global_load_dwordx4 v[46:49], v[140:141], off
	s_nop 0
	global_load_dwordx4 v[52:55], v[132:133], off
	s_waitcnt vmcnt(0) lgkmcnt(0)
	v_pk_add_f32 v[48:49], v[48:49], 1.0 op_sel_hi:[1,0]
	v_pk_add_f32 v[46:47], v[46:47], 1.0 op_sel_hi:[1,0]
	v_pk_fma_f32 v[48:49], v[68:69], v[48:49], v[54:55]
	v_pk_fma_f32 v[46:47], v[66:67], v[46:47], v[52:53]
	v_bfe_u32 v53, v48, 16, 1
	v_bfe_u32 v51, v46, 16, 1
	v_bfe_u32 v52, v47, 16, 1
	v_bfe_u32 v54, v49, 16, 1
	v_add3_u32 v46, v46, v51, s22
	v_add3_u32 v48, v48, v53, s22
	v_add3_u32 v47, v47, v52, s22
	v_add3_u32 v49, v49, v54, s22
	v_lshrrev_b32_e32 v46, 16, v46
	v_lshrrev_b32_e32 v48, 16, v48
	v_and_or_b32 v46, v47, s23, v46
	v_and_or_b32 v47, v49, s23, v48
	global_store_dwordx2 v[102:103], v[46:47], off offset:1536
	global_load_dwordx4 v[46:49], v[136:137], off
	s_nop 0
	global_load_dwordx4 v[52:55], v[134:135], off
	s_waitcnt vmcnt(0) lgkmcnt(0)
	v_pk_add_f32 v[48:49], v[48:49], 1.0 op_sel_hi:[1,0]
	v_pk_add_f32 v[46:47], v[46:47], 1.0 op_sel_hi:[1,0]
	v_pk_fma_f32 v[48:49], v[48:49], v[64:65], v[54:55]
	v_pk_fma_f32 v[46:47], v[46:47], v[62:63], v[52:53]
	v_bfe_u32 v53, v48, 16, 1
	v_bfe_u32 v51, v46, 16, 1
	v_bfe_u32 v52, v47, 16, 1
	v_bfe_u32 v54, v49, 16, 1
	v_add3_u32 v46, v46, v51, s22
	v_add3_u32 v48, v48, v53, s22
	v_add3_u32 v47, v47, v52, s22
	v_add3_u32 v49, v49, v54, s22
	v_lshrrev_b32_e32 v46, 16, v46
	v_lshrrev_b32_e32 v48, 16, v48
	v_and_or_b32 v46, v47, s23, v46
	v_and_or_b32 v47, v49, s23, v48
	global_store_dwordx2 v[102:103], v[46:47], off offset:2048
	global_load_dwordx4 v[46:49], v[130:131], off
	s_nop 0
	global_load_dwordx4 v[52:55], v[126:127], off
	s_waitcnt vmcnt(0) lgkmcnt(0)
	v_pk_add_f32 v[48:49], v[48:49], 1.0 op_sel_hi:[1,0]
	v_pk_add_f32 v[46:47], v[46:47], 1.0 op_sel_hi:[1,0]
	v_pk_fma_f32 v[48:49], v[48:49], v[60:61], v[54:55]
	v_pk_fma_f32 v[46:47], v[46:47], v[58:59], v[52:53]
	v_bfe_u32 v53, v48, 16, 1
	v_bfe_u32 v51, v46, 16, 1
	v_bfe_u32 v52, v47, 16, 1
	v_bfe_u32 v54, v49, 16, 1
	v_add3_u32 v46, v46, v51, s22
	v_add3_u32 v48, v48, v53, s22
	v_add3_u32 v47, v47, v52, s22
	v_add3_u32 v49, v49, v54, s22
	v_lshrrev_b32_e32 v46, 16, v46
	v_lshrrev_b32_e32 v48, 16, v48
	v_and_or_b32 v46, v47, s23, v46
	v_and_or_b32 v47, v49, s23, v48
	global_store_dwordx2 v[102:103], v[46:47], off offset:2560
	global_load_dwordx4 v[46:49], v[122:123], off
	s_nop 0
	global_load_dwordx4 v[52:55], v[118:119], off
	v_pk_add_f32 v[58:59], v[164:165], v[164:165] op_sel:[0,1] op_sel_hi:[1,0]
	v_pk_add_f32 v[60:61], v[158:159], v[160:161]
	v_mov_b32_e32 v59, v215
	s_waitcnt vmcnt(0) lgkmcnt(0)
	v_pk_add_f32 v[48:49], v[48:49], 1.0 op_sel_hi:[1,0]
	v_pk_add_f32 v[46:47], v[46:47], 1.0 op_sel_hi:[1,0]
	v_pk_fma_f32 v[48:49], v[48:49], v[56:57], v[54:55]
	v_pk_fma_f32 v[46:47], v[46:47], v[82:83], v[52:53]
	v_bfe_u32 v53, v48, 16, 1
	v_bfe_u32 v51, v46, 16, 1
	v_bfe_u32 v52, v47, 16, 1
	v_bfe_u32 v54, v49, 16, 1
	v_add3_u32 v46, v46, v51, s22
	v_add3_u32 v48, v48, v53, s22
	v_add3_u32 v47, v47, v52, s22
	v_add3_u32 v49, v49, v54, s22
	v_lshrrev_b32_e32 v46, 16, v46
	v_lshrrev_b32_e32 v48, 16, v48
	v_and_or_b32 v46, v47, s23, v46
	v_and_or_b32 v47, v49, s23, v48
	global_store_dwordx2 v[102:103], v[46:47], off offset:3072
	global_load_dwordx4 v[46:49], v[116:117], off
	s_nop 0
	global_load_dwordx4 v[52:55], v[114:115], off
	v_pk_add_f32 v[56:57], v[162:163], v[162:163] op_sel:[0,1] op_sel_hi:[1,0]
	s_waitcnt vmcnt(0) lgkmcnt(0)
	v_pk_add_f32 v[48:49], v[48:49], 1.0 op_sel_hi:[1,0]
	v_pk_add_f32 v[46:47], v[46:47], 1.0 op_sel_hi:[1,0]
	v_pk_fma_f32 v[48:49], v[86:87], v[48:49], v[54:55]
	v_pk_fma_f32 v[46:47], v[84:85], v[46:47], v[52:53]
	v_bfe_u32 v53, v48, 16, 1
	v_bfe_u32 v51, v46, 16, 1
	v_bfe_u32 v52, v47, 16, 1
	v_bfe_u32 v54, v49, 16, 1
	v_add3_u32 v46, v46, v51, s22
	v_add3_u32 v48, v48, v53, s22
	v_add3_u32 v47, v47, v52, s22
	v_add3_u32 v49, v49, v54, s22
	v_lshrrev_b32_e32 v46, 16, v46
	v_lshrrev_b32_e32 v48, 16, v48
	v_and_or_b32 v46, v47, s23, v46
	v_and_or_b32 v47, v49, s23, v48
	global_store_dwordx2 v[102:103], v[46:47], off offset:3584
	global_load_dwordx4 v[46:49], v[156:157], off
	s_nop 0
	global_load_dwordx4 v[52:55], v[112:113], off
	v_mov_b32_e32 v57, v214
	s_waitcnt vmcnt(0) lgkmcnt(0)
	v_pk_add_f32 v[48:49], v[48:49], 1.0 op_sel_hi:[1,0]
	v_pk_add_f32 v[46:47], v[46:47], 1.0 op_sel_hi:[1,0]
	v_pk_fma_f32 v[48:49], v[48:49], v[174:175], v[54:55]
	v_pk_fma_f32 v[46:47], v[46:47], v[88:89], v[52:53]
	v_bfe_u32 v53, v48, 16, 1
	v_bfe_u32 v51, v46, 16, 1
	v_bfe_u32 v52, v47, 16, 1
	v_bfe_u32 v54, v49, 16, 1
	v_add3_u32 v46, v46, v51, s22
	v_add3_u32 v48, v48, v53, s22
	v_add3_u32 v47, v47, v52, s22
	v_add3_u32 v49, v49, v54, s22
	v_lshrrev_b32_e32 v46, 16, v46
	v_lshrrev_b32_e32 v48, 16, v48
	v_and_or_b32 v46, v47, s23, v46
	v_and_or_b32 v47, v49, s23, v48
	global_store_dwordx2 v[104:105], v[46:47], off
	global_load_dwordx4 v[46:49], v[154:155], off
	s_nop 0
	global_load_dwordx4 v[52:55], v[106:107], off
	v_pk_mul_f32 v[44:45], v[44:45], v[50:51] op_sel_hi:[1,0]
	v_pk_mul_f32 v[42:43], v[42:43], v[50:51] op_sel_hi:[1,0]
	v_pk_mul_f32 v[44:45], v[8:9], v[44:45]
	v_pk_mul_f32 v[42:43], v[6:7], v[42:43]
	s_waitcnt vmcnt(0) lgkmcnt(0)
	v_pk_add_f32 v[48:49], v[48:49], 1.0 op_sel_hi:[1,0]
	v_pk_add_f32 v[46:47], v[46:47], 1.0 op_sel_hi:[1,0]
	v_pk_fma_f32 v[44:45], v[48:49], v[44:45], v[54:55]
	v_pk_fma_f32 v[42:43], v[46:47], v[42:43], v[52:53]
	v_bfe_u32 v48, v44, 16, 1
	v_bfe_u32 v46, v42, 16, 1
	v_bfe_u32 v47, v43, 16, 1
	v_bfe_u32 v49, v45, 16, 1
	v_add3_u32 v42, v42, v46, s22
	v_add3_u32 v44, v44, v48, s22
	v_add3_u32 v43, v43, v47, s22
	v_add3_u32 v45, v45, v49, s22
	v_lshrrev_b32_e32 v42, 16, v42
	v_lshrrev_b32_e32 v44, 16, v44
	v_and_or_b32 v42, v43, s23, v42
	v_and_or_b32 v43, v45, s23, v44
	global_store_dwordx2 v[104:105], v[42:43], off offset:512
	global_load_dwordx4 v[42:45], v[150:151], off
	s_nop 0
	global_load_dwordx4 v[46:49], v[110:111], off
	v_pk_add_f32 v[52:53], v[56:57], v[58:59]
	s_waitcnt vmcnt(0) lgkmcnt(0)
	v_pk_add_f32 v[44:45], v[44:45], 1.0 op_sel_hi:[1,0]
	v_pk_add_f32 v[52:53], v[52:53], v[60:61]
	v_pk_add_f32 v[42:43], v[42:43], 1.0 op_sel_hi:[1,0]
	v_add_f32_e32 v51, v52, v53
	ds_bpermute_b32 v52, v1, v51
	s_waitcnt lgkmcnt(0)
	v_add_f32_e32 v51, v51, v52
	ds_bpermute_b32 v52, v167, v51
	s_waitcnt lgkmcnt(0)
	v_add_f32_e32 v51, v51, v52
	v_pk_mul_f32 v[40:41], v[40:41], v[50:51] op_sel_hi:[1,0]
	v_pk_mul_f32 v[38:39], v[38:39], v[50:51] op_sel_hi:[1,0]
	v_pk_mul_f32 v[40:41], v[12:13], v[40:41]
	v_pk_mul_f32 v[38:39], v[10:11], v[38:39]
	v_pk_fma_f32 v[40:41], v[44:45], v[40:41], v[48:49]
	v_pk_fma_f32 v[38:39], v[42:43], v[38:39], v[46:47]
	v_bfe_u32 v44, v40, 16, 1
	v_bfe_u32 v42, v38, 16, 1
	v_bfe_u32 v43, v39, 16, 1
	v_bfe_u32 v45, v41, 16, 1
	v_add3_u32 v38, v38, v42, s22
	v_add3_u32 v40, v40, v44, s22
	v_add3_u32 v39, v39, v43, s22
	v_add3_u32 v41, v41, v45, s22
	v_lshrrev_b32_e32 v38, 16, v38
	v_lshrrev_b32_e32 v40, 16, v40
	v_and_or_b32 v38, v39, s23, v38
	v_and_or_b32 v39, v41, s23, v40
	global_store_dwordx2 v[104:105], v[38:39], off offset:1024
	global_load_dwordx4 v[38:41], v[138:139], off
	s_nop 0
	global_load_dwordx4 v[42:45], v[108:109], off
	v_pk_mul_f32 v[36:37], v[36:37], v[50:51] op_sel_hi:[1,0]
	v_pk_mul_f32 v[34:35], v[34:35], v[50:51] op_sel_hi:[1,0]
	v_pk_mul_f32 v[36:37], v[16:17], v[36:37]
	v_pk_mul_f32 v[34:35], v[14:15], v[34:35]
	ds_bpermute_b32 v46, v168, v51
	s_waitcnt lgkmcnt(0)
	v_add_f32_e32 v46, v51, v46
	ds_bpermute_b32 v47, v169, v46
	s_waitcnt lgkmcnt(0)
	v_add_f32_e32 v46, v46, v47
	ds_bpermute_b32 v47, v170, v46
	s_waitcnt lgkmcnt(0)
	v_add_f32_e32 v46, v46, v47
	ds_bpermute_b32 v47, v171, v46
	s_waitcnt lgkmcnt(0)
	v_add_f32_e32 v46, v46, v47
	v_fmamk_f32 v46, v46, 0x3a800000, v172
	v_mul_f32_e32 v47, 0x4f800000, v46
	v_cmp_gt_f32_e32 vcc, s13, v46
	s_waitcnt vmcnt(0)
	v_pk_add_f32 v[40:41], v[40:41], 1.0 op_sel_hi:[1,0]
	v_pk_add_f32 v[38:39], v[38:39], 1.0 op_sel_hi:[1,0]
	v_pk_fma_f32 v[36:37], v[36:37], v[40:41], v[44:45]
	v_pk_fma_f32 v[34:35], v[34:35], v[38:39], v[42:43]
	v_bfe_u32 v40, v36, 16, 1
	v_bfe_u32 v38, v34, 16, 1
	v_bfe_u32 v39, v35, 16, 1
	v_bfe_u32 v41, v37, 16, 1
	v_add3_u32 v34, v34, v38, s22
	v_add3_u32 v36, v36, v40, s22
	v_add3_u32 v35, v35, v39, s22
	v_add3_u32 v37, v37, v41, s22
	v_lshrrev_b32_e32 v34, 16, v34
	v_lshrrev_b32_e32 v36, 16, v36
	v_and_or_b32 v34, v35, s23, v34
	v_and_or_b32 v35, v37, s23, v36
	global_store_dwordx2 v[104:105], v[34:35], off offset:1536
	global_load_dwordx4 v[34:37], v[144:145], off
	s_nop 0
	global_load_dwordx4 v[38:41], v[128:129], off
	v_cndmask_b32_e32 v42, v46, v47, vcc
	v_sqrt_f32_e32 v43, v42
	s_waitcnt vmcnt(0) lgkmcnt(0)
	v_pk_add_f32 v[36:37], v[36:37], 1.0 op_sel_hi:[1,0]
	v_add_u32_e32 v44, -1, v43
	v_add_u32_e32 v45, 1, v43
	v_fma_f32 v46, -v44, v43, v42
	v_fma_f32 v47, -v45, v43, v42
	v_cmp_ge_f32_e64 s[6:7], 0, v46
	v_pk_add_f32 v[34:35], v[34:35], 1.0 op_sel_hi:[1,0]
	s_nop 0
	v_cndmask_b32_e64 v43, v43, v44, s[6:7]
	v_cmp_lt_f32_e64 s[6:7], 0, v47
	s_nop 1
	v_cndmask_b32_e64 v43, v43, v45, s[6:7]
	v_mul_f32_e32 v44, 0x37800000, v43
	v_cndmask_b32_e32 v43, v43, v44, vcc
	v_cmp_class_f32_e32 vcc, v42, v173
	s_nop 1
	v_cndmask_b32_e32 v42, v43, v42, vcc
	v_div_scale_f32 v43, s[6:7], v42, v42, 1.0
	v_rcp_f32_e32 v45, v43
	v_div_scale_f32 v44, vcc, 1.0, v42, 1.0
	v_fma_f32 v46, -v43, v45, 1.0
	v_fmac_f32_e32 v45, v46, v45
	v_mul_f32_e32 v46, v44, v45
	v_fma_f32 v47, -v43, v46, v44
	v_fmac_f32_e32 v46, v47, v45
	v_fma_f32 v43, -v43, v46, v44
	v_div_fmas_f32 v43, v43, v45, v46
	v_div_fixup_f32 v42, v43, v42, 1.0
	v_pk_mul_f32 v[32:33], v[32:33], v[42:43] op_sel_hi:[1,0]
	v_pk_mul_f32 v[30:31], v[30:31], v[42:43] op_sel_hi:[1,0]
	v_pk_mul_f32 v[32:33], v[4:5], v[32:33]
	v_pk_mul_f32 v[30:31], v[2:3], v[30:31]
	v_pk_fma_f32 v[32:33], v[36:37], v[32:33], v[40:41]
	v_pk_fma_f32 v[30:31], v[34:35], v[30:31], v[38:39]
	v_bfe_u32 v36, v32, 16, 1
	v_bfe_u32 v34, v30, 16, 1
	v_bfe_u32 v35, v31, 16, 1
	v_bfe_u32 v37, v33, 16, 1
	v_add3_u32 v30, v30, v34, s22
	v_add3_u32 v32, v32, v36, s22
	v_add3_u32 v31, v31, v35, s22
	v_add3_u32 v33, v33, v37, s22
	v_lshrrev_b32_e32 v30, 16, v30
	v_lshrrev_b32_e32 v32, 16, v32
	v_and_or_b32 v30, v31, s23, v30
	v_and_or_b32 v31, v33, s23, v32
	global_store_dwordx2 v[104:105], v[30:31], off offset:2048
	global_load_dwordx4 v[30:33], v[124:125], off
	s_nop 0
	global_load_dwordx4 v[34:37], v[120:121], off
	v_pk_mul_f32 v[28:29], v[28:29], v[42:43] op_sel_hi:[1,0]
	v_pk_mul_f32 v[26:27], v[26:27], v[42:43] op_sel_hi:[1,0]
	v_pk_mul_f32 v[28:29], v[8:9], v[28:29]
	v_pk_mul_f32 v[26:27], v[6:7], v[26:27]
	v_lshl_add_u64 v[40:41], s[20:21], 0, v[98:99]
	v_lshl_add_u64 v[38:39], s[18:19], 0, v[98:99]
	v_pk_mul_f32 v[24:25], v[24:25], v[42:43] op_sel_hi:[1,0]
	v_pk_mul_f32 v[22:23], v[22:23], v[42:43] op_sel_hi:[1,0]
	v_pk_mul_f32 v[24:25], v[12:13], v[24:25]
	v_pk_mul_f32 v[22:23], v[10:11], v[22:23]
	v_pk_mul_f32 v[20:21], v[20:21], v[42:43] op_sel_hi:[1,0]
	v_pk_mul_f32 v[18:19], v[18:19], v[42:43] op_sel_hi:[1,0]
	v_pk_mul_f32 v[20:21], v[16:17], v[20:21]
	v_pk_mul_f32 v[18:19], v[14:15], v[18:19]
	s_waitcnt vmcnt(0) lgkmcnt(0)
	v_pk_add_f32 v[32:33], v[32:33], 1.0 op_sel_hi:[1,0]
	v_pk_add_f32 v[30:31], v[30:31], 1.0 op_sel_hi:[1,0]
	v_pk_fma_f32 v[28:29], v[32:33], v[28:29], v[36:37]
	v_pk_fma_f32 v[26:27], v[30:31], v[26:27], v[34:35]
	v_bfe_u32 v32, v28, 16, 1
	v_bfe_u32 v30, v26, 16, 1
	v_bfe_u32 v31, v27, 16, 1
	v_bfe_u32 v33, v29, 16, 1
	v_add3_u32 v26, v26, v30, s22
	v_add3_u32 v28, v28, v32, s22
	v_add3_u32 v27, v27, v31, s22
	v_add3_u32 v29, v29, v33, s22
	v_lshrrev_b32_e32 v26, 16, v26
	v_lshrrev_b32_e32 v28, 16, v28
	v_and_or_b32 v26, v27, s23, v26
	v_and_or_b32 v27, v29, s23, v28
	global_store_dwordx2 v[104:105], v[26:27], off offset:2560
	global_load_dwordx4 v[26:29], v[40:41], off
	s_nop 0
	global_load_dwordx4 v[30:33], v[38:39], off
	v_lshl_add_u64 v[36:37], s[20:21], 0, v[100:101]
	v_lshl_add_u64 v[34:35], s[18:19], 0, v[100:101]
	s_waitcnt vmcnt(0) lgkmcnt(0)
	v_pk_add_f32 v[28:29], v[28:29], 1.0 op_sel_hi:[1,0]
	v_pk_add_f32 v[26:27], v[26:27], 1.0 op_sel_hi:[1,0]
	v_pk_fma_f32 v[24:25], v[28:29], v[24:25], v[32:33]
	v_pk_fma_f32 v[22:23], v[26:27], v[22:23], v[30:31]
	v_bfe_u32 v28, v24, 16, 1
	v_bfe_u32 v26, v22, 16, 1
	v_bfe_u32 v27, v23, 16, 1
	v_bfe_u32 v29, v25, 16, 1
	v_add3_u32 v22, v22, v26, s22
	v_add3_u32 v24, v24, v28, s22
	v_add3_u32 v23, v23, v27, s22
	v_add3_u32 v25, v25, v29, s22
	v_lshrrev_b32_e32 v22, 16, v22
	v_lshrrev_b32_e32 v24, 16, v24
	v_and_or_b32 v22, v23, s23, v22
	v_and_or_b32 v23, v25, s23, v24
	global_store_dwordx2 v[104:105], v[22:23], off offset:3072
	global_load_dwordx4 v[22:25], v[36:37], off
	s_nop 0
	global_load_dwordx4 v[26:29], v[34:35], off
	s_waitcnt vmcnt(0) lgkmcnt(0)
	v_pk_add_f32 v[24:25], v[24:25], 1.0 op_sel_hi:[1,0]
	v_pk_add_f32 v[22:23], v[22:23], 1.0 op_sel_hi:[1,0]
	v_pk_fma_f32 v[20:21], v[20:21], v[24:25], v[28:29]
	v_pk_fma_f32 v[18:19], v[18:19], v[22:23], v[26:27]
	v_bfe_u32 v24, v20, 16, 1
	v_bfe_u32 v22, v18, 16, 1
	v_bfe_u32 v23, v19, 16, 1
	v_bfe_u32 v25, v21, 16, 1
	v_add3_u32 v18, v18, v22, s22
	v_add3_u32 v20, v20, v24, s22
	v_add3_u32 v19, v19, v23, s22
	v_add3_u32 v21, v21, v25, s22
	v_lshrrev_b32_e32 v18, 16, v18
	v_lshrrev_b32_e32 v20, 16, v20
	v_and_or_b32 v18, v19, s23, v18
	v_and_or_b32 v19, v21, s23, v20
	global_store_dwordx2 v[104:105], v[18:19], off offset:3584
	s_cbranch_scc1 .LBB0_5544

.LBB0_5564:
	s_or_b64 exec, exec, s[76:77]
	s_lshl_b32 s9, s8, 4
	s_lshl_b32 s36, s8, 6
	s_and_b32 s9, s9, 0xffffe000
	s_and_b32 s36, s36, 0x1fc0
	s_or_b32 s36, s9, s36
	s_ashr_i32 s9, s8, 31
	s_bfe_u32 s35, s8, 0x20007
	s_lshl_b64 s[42:43], s[8:9], 14
	s_lshl_b32 s37, s35, 6
	v_add_u32_e32 v2, s36, v67
	v_mov_b64_e32 v[26:27], s[12:13]
	v_lshl_add_u64 v[4:5], v[56:57], 0, s[42:43]
	v_add_u32_e32 v10, s36, v68
	v_mad_i64_i32 v[2:3], s[44:45], v2, s29, v[26:27]
	v_add_lshl_u32 v42, v55, s37, 2
	v_add_lshl_u32 v8, v66, s37, 2
	v_mov_b32_e32 v9, v43
	v_mad_i64_i32 v[10:11], s[42:43], v10, s29, v[26:27]
	v_add_co_u32_e32 v14, vcc, s30, v4
	v_lshl_add_u64 v[6:7], v[2:3], 0, v[42:43]
	v_lshl_add_u64 v[2:3], v[2:3], 0, v[8:9]
	v_lshl_add_u64 v[12:13], v[10:11], 0, v[42:43]
	v_lshl_add_u64 v[10:11], v[10:11], 0, v[8:9]
	v_addc_co_u32_e32 v15, vcc, 0, v5, vcc
	global_load_dword v34, v[4:5], off
	global_load_dword v35, v[6:7], off
	global_load_dword v36, v[2:3], off
	global_load_dword v37, v[12:13], off
	global_load_dword v38, v[10:11], off
	global_load_dword v39, v[14:15], off
	global_load_dword v40, v[14:15], off offset:2048
	global_load_dword v41, v[4:5], off offset:2048
	v_add_u32_e32 v2, s36, v69
	v_mad_i64_i32 v[2:3], s[42:43], v2, s29, v[26:27]
	v_add_u32_e32 v10, s36, v70
	v_add_u32_e32 v14, s36, v71
	v_lshl_add_u64 v[6:7], v[2:3], 0, v[42:43]
	v_mad_i64_i32 v[10:11], s[42:43], v10, s29, v[26:27]
	v_mad_i64_i32 v[14:15], s[42:43], v14, s29, v[26:27]
	v_add_co_u32_e32 v16, vcc, s28, v4
	v_lshl_add_u64 v[2:3], v[2:3], 0, v[8:9]
	v_lshl_add_u64 v[12:13], v[10:11], 0, v[42:43]
	v_lshl_add_u64 v[10:11], v[10:11], 0, v[8:9]
	v_addc_co_u32_e32 v17, vcc, 0, v5, vcc
	v_lshl_add_u64 v[18:19], v[14:15], 0, v[42:43]
	v_lshl_add_u64 v[14:15], v[14:15], 0, v[8:9]
	global_load_dword v60, v[6:7], off
	global_load_dword v61, v[2:3], off
	global_load_dword v62, v[12:13], off
	global_load_dword v63, v[10:11], off
	global_load_dword v64, v[16:17], off
	global_load_dword v65, v[18:19], off
	global_load_dword v106, v[14:15], off
	global_load_dword v107, v[16:17], off offset:2048
	v_add_u32_e32 v20, s36, v72
	v_mad_i64_i32 v[20:21], s[42:43], v20, s29, v[26:27]
	v_add_u32_e32 v10, s36, v73
	v_add_u32_e32 v14, s36, v74
	v_lshl_add_u64 v[2:3], v[20:21], 0, v[42:43]
	v_mad_i64_i32 v[10:11], s[42:43], v10, s29, v[26:27]
	v_add_co_u32_e32 v4, vcc, s29, v4
	v_mad_i64_i32 v[14:15], s[42:43], v14, s29, v[26:27]
	v_lshl_add_u64 v[6:7], v[20:21], 0, v[8:9]
	v_addc_co_u32_e32 v5, vcc, 0, v5, vcc
	v_lshl_add_u64 v[12:13], v[10:11], 0, v[42:43]
	v_lshl_add_u64 v[10:11], v[10:11], 0, v[8:9]
	v_lshl_add_u64 v[16:17], v[14:15], 0, v[42:43]
	v_lshl_add_u64 v[8:9], v[14:15], 0, v[8:9]
	global_load_dword v42, v[2:3], off
	global_load_dword v108, v[6:7], off
	global_load_dword v109, v[4:5], off
	global_load_dword v110, v[12:13], off
	global_load_dword v111, v[10:11], off
	global_load_dword v112, v[16:17], off
	global_load_dword v113, v[8:9], off
	global_load_dword v114, v[4:5], off offset:2048
	s_lshl_b64 s[8:9], s[8:9], 15
	v_add_u32_e32 v2, s36, v75
	v_lshl_add_u64 v[28:29], v[44:45], 0, s[8:9]
	v_mad_i64_i32 v[2:3], s[8:9], v2, s29, v[26:27]
	s_lshl_b32 s70, s35, 9
	v_lshl_add_u64 v[2:3], v[2:3], 0, s[70:71]
	v_mov_b32_e32 v59, v43
	v_add_u32_e32 v10, s36, v76
	v_lshl_add_u64 v[2:3], v[2:3], 0, v[58:59]
	v_mad_i64_i32 v[10:11], s[8:9], v10, s29, v[26:27]
	v_add_co_u32_e32 v2, vcc, s30, v2
	v_lshl_add_u64 v[10:11], v[10:11], 0, s[70:71]
	v_add_u32_e32 v18, s36, v77
	v_addc_co_u32_e32 v3, vcc, 0, v3, vcc
	v_lshl_add_u64 v[10:11], v[10:11], 0, v[58:59]
	v_mad_i64_i32 v[18:19], s[8:9], v18, s29, v[26:27]
	v_add_co_u32_e32 v10, vcc, s30, v10
	v_lshl_add_u64 v[18:19], v[18:19], 0, s[70:71]
	v_add_u32_e32 v30, s36, v78
	v_addc_co_u32_e32 v11, vcc, 0, v11, vcc
	v_lshl_add_u64 v[18:19], v[18:19], 0, v[58:59]
	v_mad_i64_i32 v[26:27], s[8:9], v30, s29, v[26:27]
	v_add_co_u32_e32 v18, vcc, s30, v18
	v_lshl_add_u64 v[26:27], v[26:27], 0, s[70:71]
	s_nop 0
	v_addc_co_u32_e32 v19, vcc, 0, v19, vcc
	v_lshl_add_u64 v[26:27], v[26:27], 0, v[58:59]
	v_add_co_u32_e32 v26, vcc, s30, v26
	v_lshl_add_u64 v[6:7], v[46:47], 2, v[28:29]
	v_lshl_add_u64 v[14:15], v[48:49], 2, v[28:29]
	v_lshl_add_u64 v[22:23], v[50:51], 2, v[28:29]
	v_addc_co_u32_e32 v27, vcc, 0, v27, vcc
	v_lshl_add_u64 v[30:31], v[52:53], 2, v[28:29]
	global_load_dwordx4 v[2:5], v[2:3], off offset:3168
	s_nop 0
	global_load_dwordx4 v[6:9], v[6:7], off
	s_nop 0
	global_load_dwordx4 v[10:13], v[10:11], off offset:3168
	s_nop 0
	global_load_dwordx4 v[14:17], v[14:15], off
	s_nop 0
	global_load_dwordx4 v[18:21], v[18:19], off offset:3168
	s_nop 0
	global_load_dwordx4 v[22:25], v[22:23], off
	s_nop 0
	global_load_dwordx4 v[26:29], v[26:27], off offset:3168
	s_nop 0
	global_load_dwordx4 v[30:33], v[30:31], off
	s_waitcnt vmcnt(0) lgkmcnt(0)
	v_mul_f32_e32 v59, 0x3fb8aa3b, v34
	v_mul_f32_e32 v34, 0xbfb8aa3b, v34
	v_exp_f32_e32 v34, v34
	v_exp_f32_e32 v59, v59
	v_mul_f32_e32 v35, 0x3e000000, v35
	v_mul_f32_e32 v34, v36, v34
	v_mul_f32_e32 v36, 0x3fb8aa3b, v41
	v_exp_f32_e32 v36, v36
	v_mul_f32_e32 v35, v35, v59
	v_mul_f32_e32 v41, 0xbfb8aa3b, v41
	s_barrier
	v_exp_f32_e32 v41, v41
	ds_write2st64_b32 v79, v35, v34 offset0:65 offset1:130
	v_mul_f32_e32 v34, 0x3e000000, v37
	v_mul_f32_e32 v34, v34, v36
	v_mul_f32_e32 v36, 0x3fb8aa3b, v39
	v_mul_f32_e32 v37, 0xbfb8aa3b, v39
	v_exp_f32_e32 v36, v36
	v_exp_f32_e32 v37, v37
	v_mul_f32_e32 v35, v38, v41
	ds_write2st64_b32 v80, v34, v35 offset0:65 offset1:130
	v_mul_f32_e32 v34, 0x3e000000, v60
	v_mul_f32_e32 v34, v34, v36
	v_mul_f32_e32 v35, v61, v37
	v_mul_f32_e32 v36, 0x3fb8aa3b, v40
	v_mul_f32_e32 v37, 0xbfb8aa3b, v40
	v_exp_f32_e32 v36, v36
	v_exp_f32_e32 v37, v37
	ds_write2st64_b32 v81, v34, v35 offset0:65 offset1:130
	v_mul_f32_e32 v34, 0x3e000000, v62
	v_mul_f32_e32 v34, v34, v36
	v_mul_f32_e32 v35, v63, v37
	v_mul_f32_e32 v36, 0x3fb8aa3b, v64
	v_mul_f32_e32 v37, 0xbfb8aa3b, v64
	v_exp_f32_e32 v36, v36
	v_exp_f32_e32 v37, v37
	ds_write2st64_b32 v82, v34, v35 offset0:65 offset1:130
	v_mul_f32_e32 v34, 0x3e000000, v65
	v_mul_f32_e32 v34, v34, v36
	v_mul_f32_e32 v35, v106, v37
	v_mul_f32_e32 v36, 0x3fb8aa3b, v107
	v_mul_f32_e32 v37, 0xbfb8aa3b, v107
	v_exp_f32_e32 v36, v36
	v_exp_f32_e32 v37, v37
	ds_write2st64_b32 v83, v34, v35 offset0:65 offset1:130
	v_mul_f32_e32 v34, 0x3e000000, v42
	v_mul_f32_e32 v34, v34, v36
	v_mul_f32_e32 v35, v108, v37
	v_mul_f32_e32 v36, 0x3fb8aa3b, v109
	v_mul_f32_e32 v37, 0xbfb8aa3b, v109
	v_exp_f32_e32 v36, v36
	v_exp_f32_e32 v37, v37
	ds_write2st64_b32 v84, v34, v35 offset0:65 offset1:130
	v_mul_f32_e32 v34, 0x3e000000, v110
	v_mul_f32_e32 v34, v34, v36
	v_mul_f32_e32 v35, v111, v37
	v_mul_f32_e32 v36, 0x3fb8aa3b, v114
	v_mul_f32_e32 v37, 0xbfb8aa3b, v114
	v_exp_f32_e32 v36, v36
	v_exp_f32_e32 v37, v37
	ds_write2st64_b32 v85, v34, v35 offset0:65 offset1:130
	v_mul_f32_e32 v34, 0x3e000000, v112
	v_mul_f32_e32 v34, v34, v36
	v_mul_f32_e32 v35, v113, v37
	ds_write2st64_b32 v86, v34, v35 offset0:65 offset1:130
	ds_write_b128 v87, v[2:5] offset:49920
	ds_write_b128 v88, v[6:9]
	ds_write_b128 v87, v[10:13] offset:58112
	ds_write_b128 v89, v[14:17]
	ds_write_b128 v90, v[18:21]
	ds_write_b128 v91, v[22:25]
	ds_write_b128 v92, v[26:29]
	ds_write_b128 v93, v[30:33]
	v_mov_b32_e32 v2, 0
	s_lshl_b32 s35, s35, 7
	s_mov_b32 s8, 32
	v_mov_b32_e32 v18, v97
	v_mov_b32_e32 v19, v96
	v_mov_b32_e32 v3, v2
	v_mov_b32_e32 v4, v2
	v_mov_b32_e32 v5, v2
	v_mov_b32_e32 v6, v2
	v_mov_b32_e32 v7, v2
	v_mov_b32_e32 v8, v2
	v_mov_b32_e32 v9, v2
	v_mov_b32_e32 v10, v2
	v_mov_b32_e32 v11, v2
	v_mov_b32_e32 v12, v2
	v_mov_b32_e32 v13, v2
	v_mov_b32_e32 v14, v2
	v_mov_b32_e32 v15, v2
	v_mov_b32_e32 v16, v2
	v_mov_b32_e32 v17, v2
	s_waitcnt lgkmcnt(0)
	s_barrier

.LBB0_5572:
	ds_read2_b32 v[20:21], v18 offset1:2
	ds_read2st64_b32 v[22:23], v19 offset1:4
	s_add_i32 s8, s8, -8
	s_cmp_lg_u32 s8, 0
	s_waitcnt lgkmcnt(0)
	v_mfma_f32_32x32x2_f32 v[2:17], v20, v22, v[2:17]
	v_mfma_f32_32x32x2_f32 v[2:17], v21, v23, v[2:17]
	ds_read2_b32 v[20:21], v18 offset0:4 offset1:6
	ds_read2st64_b32 v[22:23], v19 offset0:8 offset1:12
	s_waitcnt lgkmcnt(0)
	v_mfma_f32_32x32x2_f32 v[2:17], v20, v22, v[2:17]
	v_mfma_f32_32x32x2_f32 v[2:17], v21, v23, v[2:17]
	ds_read2_b32 v[20:21], v18 offset0:8 offset1:10
	ds_read2st64_b32 v[22:23], v19 offset0:16 offset1:20
	s_waitcnt lgkmcnt(0)
	v_mfma_f32_32x32x2_f32 v[2:17], v20, v22, v[2:17]
	v_mfma_f32_32x32x2_f32 v[2:17], v21, v23, v[2:17]
	ds_read2_b32 v[20:21], v18 offset0:12 offset1:14
	ds_read2st64_b32 v[22:23], v19 offset0:24 offset1:28
	v_add_u32_e32 v19, 0x2000, v19
	v_add_u32_e32 v18, 64, v18
	s_waitcnt lgkmcnt(0)
	v_mfma_f32_32x32x2_f32 v[2:17], v20, v22, v[2:17]
	v_mfma_f32_32x32x2_f32 v[2:17], v21, v23, v[2:17]
	s_cbranch_scc1 .LBB0_5572
	v_add_u32_e32 v18, 0xc200, v103
	s_barrier
	s_nop 14
	ds_write2_b32 v18, v2, v3 offset0:64 offset1:196
	v_add_u32_e32 v2, 0xc600, v103
	ds_write2_b32 v2, v4, v5 offset0:72 offset1:204
	v_add_u32_e32 v2, 0xd200, v103
	ds_write2_b32 v2, v6, v7 offset0:96 offset1:228
	v_add_u32_e32 v2, 0xd600, v103
	ds_write2_b32 v2, v8, v9 offset0:104 offset1:236
	v_add_u32_e32 v2, 0xe400, v103
	ds_write2_b32 v2, v10, v11 offset1:132
	v_add_u32_e32 v2, 0xe800, v103
	ds_write2_b32 v2, v12, v13 offset0:8 offset1:140
	v_add_u32_e32 v2, 0xf400, v103
	ds_write2_b32 v2, v14, v15 offset0:32 offset1:164
	v_add_u32_e32 v2, 0xf800, v103
	v_mov_b64_e32 v[18:19], s[0:1]
	ds_write2_b32 v2, v16, v17 offset0:40 offset1:172
	s_waitcnt lgkmcnt(0)
	s_barrier
	ds_read_b128 v[14:17], v95 offset:49920
	ds_read_b128 v[10:13], v95 offset:49936
	ds_read_b128 v[6:9], v95 offset:49952
	ds_read_b128 v[2:5], v95 offset:49968
	global_load_dwordx2 v[22:23], v[18:19], off offset:168 sc0 sc1
	s_waitcnt vmcnt(0)
	v_add_u32_e32 v60, s36, v94
	v_mov_b64_e32 v[18:19], s[12:13]
	v_and_b32_e32 v21, 64, v166
	s_lshl_b32 s70, s35, 2
	v_mad_i64_i32 v[18:19], s[8:9], v60, s29, v[18:19]
	v_xor_b32_e32 v20, 1, v166
	v_lshlrev_b32_e32 v42, 2, v54
	v_add_u32_e32 v59, 64, v21
	v_lshl_add_u64 v[18:19], v[18:19], 0, s[70:71]
	v_cmp_lt_i32_e32 vcc, v20, v59
	v_lshl_add_u64 v[30:31], v[18:19], 0, v[42:43]
	s_waitcnt lgkmcnt(0)
	v_mov_b32_e32 v26, v15
	v_cndmask_b32_e32 v20, v166, v20, vcc
	v_add_co_u32_e32 v18, vcc, s28, v30
	v_lshlrev_b32_e32 v61, 2, v20
	s_nop 0
	v_addc_co_u32_e32 v19, vcc, 0, v31, vcc
	global_load_dwordx4 v[18:21], v[18:19], off offset:1184
	v_mov_b32_e32 v27, v11
	v_mov_b32_e32 v24, v14
	v_mov_b32_e32 v25, v10
	v_mov_b32_e32 v36, v7
	v_mov_b32_e32 v37, v3
	v_pk_mul_f32 v[26:27], v[26:27], v[26:27]
	v_mov_b32_e32 v28, v16
	v_mov_b32_e32 v29, v12
	v_mov_b32_e32 v34, v6
	v_mov_b32_e32 v35, v2
	v_pk_mul_f32 v[36:37], v[36:37], v[36:37]
	v_pk_fma_f32 v[24:25], v[24:25], v[24:25], v[26:27]
	v_mov_b32_e32 v32, v17
	v_mov_b32_e32 v33, v13
	v_mov_b32_e32 v38, v8
	v_mov_b32_e32 v39, v4
	v_pk_fma_f32 v[26:27], v[34:35], v[34:35], v[36:37]
	v_pk_fma_f32 v[24:25], v[28:29], v[28:29], v[24:25]
	v_mov_b32_e32 v40, v9
	v_mov_b32_e32 v41, v5
	v_pk_fma_f32 v[26:27], v[38:39], v[38:39], v[26:27]
	v_pk_fma_f32 v[24:25], v[32:33], v[32:33], v[24:25]
	v_pk_fma_f32 v[26:27], v[40:41], v[40:41], v[26:27]
	v_add_f32_e32 v24, v24, v25
	v_add_f32_e32 v24, v24, v26
	v_add_f32_e32 v24, v24, v27
	ds_bpermute_b32 v25, v61, v24
	v_xor_b32_e32 v26, 2, v166
	v_cmp_lt_i32_e32 vcc, v26, v59
	v_lshl_add_u64 v[62:63], v[30:31], 0, s[72:73]
	v_mov_b32_e32 v38, v14
	v_cndmask_b32_e32 v26, v166, v26, vcc
	v_lshlrev_b32_e32 v26, 2, v26
	s_waitcnt lgkmcnt(0)
	v_add_f32_e32 v24, v24, v25
	ds_bpermute_b32 v25, v26, v24
	v_ashrrev_i32_e32 v61, 31, v60
	s_lshl_b32 s70, s35, 1
	s_mov_b64 s[76:77], 0
	s_waitcnt lgkmcnt(0)
	v_add_f32_e32 v32, v24, v25
	v_lshl_add_u64 v[64:65], v[22:23], 0, v[42:43]
	global_load_dwordx4 v[26:29], v[64:65], off offset:512
	v_xor_b32_e32 v22, 4, v166
	v_cmp_lt_i32_e32 vcc, v22, v59
	s_nop 1
	v_cndmask_b32_e32 v22, v166, v22, vcc
	v_lshlrev_b32_e32 v22, 2, v22
	ds_bpermute_b32 v33, v22, v32
	global_load_dwordx4 v[22:25], v[64:65], off offset:528
	s_waitcnt lgkmcnt(0)
	v_add_f32_e32 v30, v32, v33
	v_fmamk_f32 v30, v30, 0x3c000000, v104
	v_mul_f32_e32 v31, 0x4f800000, v30
	v_cmp_gt_f32_e32 vcc, s31, v30
	s_nop 1
	v_cndmask_b32_e32 v39, v30, v31, vcc
	v_sqrt_f32_e32 v40, v39
	global_load_dwordx4 v[30:33], v[62:63], off offset:16
	global_load_dwordx4 v[34:37], v[62:63], off offset:48
	v_add_u32_e32 v14, -1, v40
	v_add_u32_e32 v41, 1, v40
	v_fma_f32 v42, -v14, v40, v39
	v_fma_f32 v59, -v41, v40, v39
	v_cmp_ge_f32_e64 s[8:9], 0, v42
	s_nop 1
	v_cndmask_b32_e64 v14, v40, v14, s[8:9]
	v_cmp_lt_f32_e64 s[8:9], 0, v59
	s_nop 1
	v_cndmask_b32_e64 v14, v14, v41, s[8:9]
	v_mul_f32_e32 v40, 0x37800000, v14
	v_cndmask_b32_e32 v14, v14, v40, vcc
	v_cmp_class_f32_e32 vcc, v39, v105
	s_nop 1
	v_cndmask_b32_e32 v14, v14, v39, vcc
	v_div_scale_f32 v40, s[8:9], v14, v14, 1.0
	v_rcp_f32_e32 v41, v40
	v_mov_b32_e32 v39, v16
	v_div_scale_f32 v16, vcc, 1.0, v14, 1.0
	v_fma_f32 v42, -v40, v41, 1.0
	v_fmac_f32_e32 v41, v42, v41
	v_mul_f32_e32 v42, v16, v41
	v_fma_f32 v59, -v40, v42, v16
	v_fmac_f32_e32 v42, v59, v41
	v_fma_f32 v16, -v40, v42, v16
	v_div_fmas_f32 v16, v16, v41, v42
	v_div_fixup_f32 v14, v16, v14, 1.0
	v_pk_mul_f32 v[110:111], v[38:39], v[14:15] op_sel_hi:[1,0]
	s_waitcnt vmcnt(0)
	v_mul_f32_e32 v16, 0xbfb8aa3b, v18
	v_mul_f32_e32 v38, 0xbfb8aa3b, v20
	v_exp_f32_e32 v112, v16
	v_exp_f32_e32 v113, v38
	v_mul_f32_e32 v16, 0xbfb8aa3b, v19
	global_load_dwordx4 v[38:41], v[64:65], off offset:560
	global_load_dwordx4 v[106:109], v[64:65], off offset:544
	v_exp_f32_e32 v64, v16
	v_pk_add_f32 v[112:113], v[112:113], 1.0 op_sel_hi:[1,0]
	s_nop 0
	v_div_scale_f32 v16, s[8:9], v113, v113, v20
	v_rcp_f32_e32 v65, v16
	v_div_scale_f32 v59, s[8:9], v112, v112, v18
	v_rcp_f32_e32 v116, v59
	v_fma_f32 v114, -v16, v65, 1.0
	v_div_scale_f32 v42, vcc, v20, v113, v20
	v_fmac_f32_e32 v65, v114, v65
	v_fma_f32 v115, -v59, v116, 1.0
	v_mul_f32_e32 v114, v42, v65
	v_fmac_f32_e32 v116, v115, v116
	v_fma_f32 v115, -v16, v114, v42
	v_fmac_f32_e32 v114, v115, v65
	v_fma_f32 v16, -v16, v114, v42
	v_div_fmas_f32 v16, v16, v65, v114
	v_div_scale_f32 v117, s[8:9], v18, v112, v18
	v_div_fixup_f32 v113, v16, v113, v20
	v_mul_f32_e32 v20, 0xbfb8aa3b, v21
	v_mul_f32_e32 v118, v117, v116
	v_exp_f32_e32 v65, v20
	v_fma_f32 v119, -v59, v118, v117
	v_fmac_f32_e32 v118, v119, v116
	v_fma_f32 v16, -v59, v118, v117
	s_mov_b64 vcc, s[8:9]
	v_div_fmas_f32 v16, v16, v116, v118
	v_pk_add_f32 v[64:65], v[64:65], 1.0 op_sel_hi:[1,0]
	v_div_fixup_f32 v112, v16, v112, v18
	v_mov_b32_e32 v16, v15
	v_div_scale_f32 v15, s[8:9], v65, v65, v21
	v_rcp_f32_e32 v18, v15
	v_mov_b32_e32 v114, v26
	v_mov_b32_e32 v115, v28
	v_mov_b32_e32 v28, v27
	v_fma_f32 v20, -v15, v18, 1.0
	v_fmac_f32_e32 v18, v20, v18
	v_div_scale_f32 v20, vcc, v21, v65, v21
	v_mul_f32_e32 v26, v20, v18
	v_fma_f32 v27, -v15, v26, v20
	v_fmac_f32_e32 v26, v27, v18
	v_pk_mul_f32 v[16:17], v[16:17], v[14:15] op_sel_hi:[1,0]
	v_fma_f32 v15, -v15, v26, v20
	v_div_scale_f32 v20, s[8:9], v64, v64, v19
	v_rcp_f32_e32 v27, v20
	v_div_fmas_f32 v15, v15, v18, v26
	v_div_fixup_f32 v21, v15, v65, v21
	v_pk_mul_f32 v[16:17], v[28:29], v[16:17]
	v_fma_f32 v15, -v20, v27, 1.0
	v_fmac_f32_e32 v27, v15, v27
	v_div_scale_f32 v15, vcc, v19, v64, v19
	v_mul_f32_e32 v18, v15, v27
	v_fma_f32 v26, -v20, v18, v15
	v_fmac_f32_e32 v18, v26, v27
	v_fma_f32 v15, -v20, v18, v15
	v_div_fmas_f32 v15, v15, v27, v18
	v_div_fixup_f32 v20, v15, v64, v19
	v_pk_mul_f32 v[20:21], v[20:21], v[16:17]
	global_load_dwordx4 v[16:19], v[62:63], off offset:32
	s_waitcnt lgkmcnt(0)
	v_mul_f32_e32 v15, 0xbfb8aa3b, v30
	v_exp_f32_e32 v26, v15
	v_mul_f32_e32 v15, 0xbfb8aa3b, v31
	v_exp_f32_e32 v28, v15
	v_mul_f32_e32 v15, 0xbfb8aa3b, v32
	v_exp_f32_e32 v27, v15
	v_mov_b32_e32 v62, v10
	v_mov_b32_e32 v63, v12
	v_pk_mul_f32 v[62:63], v[62:63], v[14:15] op_sel_hi:[1,0]
	v_pk_add_f32 v[26:27], v[26:27], 1.0 op_sel_hi:[1,0]
	v_mov_b32_e32 v64, v22
	v_div_scale_f32 v10, s[8:9], v27, v27, v32
	v_rcp_f32_e32 v12, v10
	v_mov_b32_e32 v65, v24
	v_pk_mul_f32 v[110:111], v[114:115], v[110:111]
	v_pk_mul_f32 v[62:63], v[62:63], v[64:65]
	v_fma_f32 v15, -v10, v12, 1.0
	v_fmac_f32_e32 v12, v15, v12
	v_div_scale_f32 v15, vcc, v32, v27, v32
	v_mul_f32_e32 v22, v15, v12
	v_fma_f32 v24, -v10, v22, v15
	v_fmac_f32_e32 v22, v24, v12
	v_fma_f32 v10, -v10, v22, v15
	v_div_scale_f32 v15, s[8:9], v26, v26, v30
	v_rcp_f32_e32 v24, v15
	v_div_fmas_f32 v10, v10, v12, v22
	v_div_fixup_f32 v27, v10, v27, v32
	v_pk_mul_f32 v[110:111], v[112:113], v[110:111]
	v_fma_f32 v10, -v15, v24, 1.0
	v_fmac_f32_e32 v24, v10, v24
	v_div_scale_f32 v10, vcc, v30, v26, v30
	v_mul_f32_e32 v12, v10, v24
	v_fma_f32 v22, -v15, v12, v10
	v_fmac_f32_e32 v12, v22, v24
	v_fma_f32 v10, -v15, v12, v10
	v_div_fmas_f32 v10, v10, v24, v12
	v_mul_f32_e32 v12, 0xbfb8aa3b, v33
	v_exp_f32_e32 v29, v12
	v_div_fixup_f32 v26, v10, v26, v30
	v_mov_b32_e32 v12, v11
	v_mov_b32_e32 v24, v23
	v_pk_add_f32 v[10:11], v[28:29], 1.0 op_sel_hi:[1,0]
	v_pk_mul_f32 v[26:27], v[62:63], v[26:27]
	v_div_scale_f32 v15, s[8:9], v11, v11, v33
	v_rcp_f32_e32 v22, v15
	v_pk_mul_f32 v[12:13], v[12:13], v[14:15] op_sel_hi:[1,0]
	v_lshlrev_b32_e32 v42, 1, v54
	v_pk_mul_f32 v[12:13], v[12:13], v[24:25]
	v_fma_f32 v23, -v15, v22, 1.0
	v_fmac_f32_e32 v22, v23, v22
	v_div_scale_f32 v23, vcc, v33, v11, v33
	v_mul_f32_e32 v24, v23, v22
	v_fma_f32 v25, -v15, v24, v23
	v_fmac_f32_e32 v24, v25, v22
	v_fma_f32 v15, -v15, v24, v23
	v_div_scale_f32 v23, s[8:9], v10, v10, v31
	v_rcp_f32_e32 v25, v23
	v_div_fmas_f32 v15, v15, v22, v24
	v_div_fixup_f32 v11, v15, v11, v33
	v_fma_f32 v15, -v23, v25, 1.0
	v_fmac_f32_e32 v25, v15, v25
	v_div_scale_f32 v15, vcc, v31, v10, v31
	v_mul_f32_e32 v22, v15, v25
	v_fma_f32 v24, -v23, v22, v15
	v_fmac_f32_e32 v22, v24, v25
	v_fma_f32 v15, -v23, v22, v15
	v_div_fmas_f32 v15, v15, v25, v22
	v_div_fixup_f32 v10, v15, v10, v31
	v_pk_mul_f32 v[10:11], v[12:13], v[10:11]
	v_bfe_u32 v22, v20, 16, 1
	v_bfe_u32 v13, v10, 16, 1
	v_bfe_u32 v12, v11, 16, 1
	v_bfe_u32 v15, v21, 16, 1
	v_add3_u32 v20, v20, v22, s33
	v_add3_u32 v10, v10, v13, s33
	v_bfe_u32 v13, v111, 16, 1
	v_bfe_u32 v22, v27, 16, 1
	v_add3_u32 v15, v21, v15, s33
	v_add3_u32 v11, v11, v12, s33
	v_bfe_u32 v12, v110, 16, 1
	v_bfe_u32 v21, v26, 16, 1
	v_add3_u32 v22, v27, v22, s33
	v_add3_u32 v13, v111, v13, s33
	v_add3_u32 v21, v26, v21, s33
	v_add3_u32 v12, v110, v12, s33
	v_lshrrev_b32_e32 v24, 16, v13
	v_lshrrev_b32_e32 v13, 16, v22
	v_lshrrev_b32_e32 v23, 16, v12
	v_lshrrev_b32_e32 v12, 16, v21
	v_and_or_b32 v13, v11, s34, v13
	v_and_or_b32 v11, v15, s34, v24
	s_waitcnt vmcnt(0)
	v_mul_f32_e32 v15, 0xbfb8aa3b, v16
	v_and_or_b32 v12, v10, s34, v12
	v_and_or_b32 v10, v20, s34, v23
	v_exp_f32_e32 v20, v15
	v_mul_f32_e32 v15, 0xbfb8aa3b, v17
	v_exp_f32_e32 v22, v15
	v_mul_f32_e32 v15, 0xbfb8aa3b, v18
	v_exp_f32_e32 v21, v15
	v_mov_b32_e32 v24, v6
	v_mov_b32_e32 v25, v8
	v_pk_mul_f32 v[24:25], v[24:25], v[14:15] op_sel_hi:[1,0]
	v_pk_add_f32 v[20:21], v[20:21], 1.0 op_sel_hi:[1,0]
	v_mov_b32_e32 v26, v106
	v_div_scale_f32 v6, s[8:9], v21, v21, v18
	v_rcp_f32_e32 v8, v6
	v_mov_b32_e32 v27, v108
	v_pk_mul_f32 v[24:25], v[24:25], v[26:27]
	v_mov_b32_e32 v108, v107
	v_fma_f32 v15, -v6, v8, 1.0
	v_fmac_f32_e32 v8, v15, v8
	v_div_scale_f32 v15, vcc, v18, v21, v18
	v_mul_f32_e32 v23, v15, v8
	v_fma_f32 v26, -v6, v23, v15
	v_fmac_f32_e32 v23, v26, v8
	v_fma_f32 v6, -v6, v23, v15
	v_div_scale_f32 v15, s[8:9], v20, v20, v16
	v_rcp_f32_e32 v26, v15
	v_div_fmas_f32 v6, v6, v8, v23
	v_div_fixup_f32 v21, v6, v21, v18
	v_fma_f32 v6, -v15, v26, 1.0
	v_fmac_f32_e32 v26, v6, v26
	v_div_scale_f32 v6, vcc, v16, v20, v16
	v_mul_f32_e32 v8, v6, v26
	v_fma_f32 v18, -v15, v8, v6
	v_fmac_f32_e32 v8, v18, v26
	v_fma_f32 v6, -v15, v8, v6
	v_div_fmas_f32 v6, v6, v26, v8
	v_mul_f32_e32 v8, 0xbfb8aa3b, v19
	v_exp_f32_e32 v23, v8
	v_div_fixup_f32 v20, v6, v20, v16
	v_mov_b32_e32 v8, v7
	v_pk_mul_f32 v[20:21], v[24:25], v[20:21]
	v_pk_add_f32 v[6:7], v[22:23], 1.0 op_sel_hi:[1,0]
	s_nop 0
	v_div_scale_f32 v15, s[8:9], v7, v7, v19
	v_rcp_f32_e32 v16, v15
	v_pk_mul_f32 v[8:9], v[8:9], v[14:15] op_sel_hi:[1,0]
	v_fma_f32 v18, -v15, v16, 1.0
	v_fmac_f32_e32 v16, v18, v16
	v_div_scale_f32 v18, vcc, v19, v7, v19
	v_mul_f32_e32 v22, v18, v16
	v_fma_f32 v23, -v15, v22, v18
	v_fmac_f32_e32 v22, v23, v16
	v_fma_f32 v15, -v15, v22, v18
	v_div_scale_f32 v18, s[8:9], v6, v6, v17
	v_rcp_f32_e32 v23, v18
	v_div_fmas_f32 v15, v15, v16, v22
	v_div_fixup_f32 v7, v15, v7, v19
	v_pk_mul_f32 v[8:9], v[8:9], v[108:109]
	v_fma_f32 v15, -v18, v23, 1.0
	v_fmac_f32_e32 v23, v15, v23
	v_div_scale_f32 v15, vcc, v17, v6, v17
	v_mul_f32_e32 v16, v15, v23
	v_fma_f32 v19, -v18, v16, v15
	v_fmac_f32_e32 v16, v19, v23
	v_fma_f32 v15, -v18, v16, v15
	v_div_fmas_f32 v15, v15, v23, v16
	v_div_fixup_f32 v6, v15, v6, v17
	v_pk_mul_f32 v[6:7], v[8:9], v[6:7]
	v_mul_f32_e32 v9, 0xbfb8aa3b, v35
	v_mul_f32_e32 v8, 0xbfb8aa3b, v34
	v_exp_f32_e32 v16, v9
	v_mul_f32_e32 v9, 0xbfb8aa3b, v36
	v_exp_f32_e32 v8, v8
	v_exp_f32_e32 v9, v9
	v_mov_b32_e32 v18, v2
	v_mov_b32_e32 v19, v4
	v_pk_mul_f32 v[18:19], v[18:19], v[14:15] op_sel_hi:[1,0]
	v_pk_add_f32 v[8:9], v[8:9], 1.0 op_sel_hi:[1,0]
	v_mov_b32_e32 v22, v38
	v_div_scale_f32 v2, s[8:9], v9, v9, v36
	v_rcp_f32_e32 v4, v2
	v_mov_b32_e32 v23, v40
	v_pk_mul_f32 v[18:19], v[18:19], v[22:23]
	v_mov_b32_e32 v40, v39
	v_fma_f32 v15, -v2, v4, 1.0
	v_fmac_f32_e32 v4, v15, v4
	v_div_scale_f32 v15, vcc, v36, v9, v36
	v_mul_f32_e32 v17, v15, v4
	v_fma_f32 v22, -v2, v17, v15
	v_fmac_f32_e32 v17, v22, v4
	v_fma_f32 v2, -v2, v17, v15
	v_div_scale_f32 v15, s[8:9], v8, v8, v34
	v_rcp_f32_e32 v22, v15
	v_div_fmas_f32 v2, v2, v4, v17
	v_div_fixup_f32 v9, v2, v9, v36
	v_fma_f32 v2, -v15, v22, 1.0
	v_fmac_f32_e32 v22, v2, v22
	v_div_scale_f32 v2, vcc, v34, v8, v34
	v_mul_f32_e32 v4, v2, v22
	v_fma_f32 v17, -v15, v4, v2
	v_fmac_f32_e32 v4, v17, v22
	v_fma_f32 v2, -v15, v4, v2
	v_div_fmas_f32 v2, v2, v22, v4
	v_mul_f32_e32 v4, 0xbfb8aa3b, v37
	v_exp_f32_e32 v17, v4
	v_div_fixup_f32 v8, v2, v8, v34
	v_mov_b32_e32 v4, v3
	v_pk_mul_f32 v[8:9], v[18:19], v[8:9]
	v_pk_add_f32 v[2:3], v[16:17], 1.0 op_sel_hi:[1,0]
	s_nop 0
	v_div_scale_f32 v15, s[8:9], v3, v3, v37
	v_rcp_f32_e32 v16, v15
	v_pk_mul_f32 v[4:5], v[4:5], v[14:15] op_sel_hi:[1,0]
	v_fma_f32 v14, -v15, v16, 1.0
	v_fmac_f32_e32 v16, v14, v16
	v_div_scale_f32 v14, vcc, v37, v3, v37
	v_mul_f32_e32 v17, v14, v16
	v_fma_f32 v18, -v15, v17, v14
	v_fmac_f32_e32 v17, v18, v16
	v_fma_f32 v14, -v15, v17, v14
	v_div_scale_f32 v15, s[8:9], v2, v2, v35
	v_rcp_f32_e32 v18, v15
	v_div_fmas_f32 v14, v14, v16, v17
	v_div_fixup_f32 v3, v14, v3, v37
	v_pk_mul_f32 v[4:5], v[4:5], v[40:41]
	v_fma_f32 v14, -v15, v18, 1.0
	v_fmac_f32_e32 v18, v14, v18
	v_div_scale_f32 v14, vcc, v35, v2, v35
	v_mul_f32_e32 v16, v14, v18
	v_fma_f32 v17, -v15, v16, v14
	v_fmac_f32_e32 v16, v17, v18
	v_fma_f32 v14, -v15, v16, v14
	v_div_fmas_f32 v14, v14, v18, v16
	v_div_fixup_f32 v2, v14, v2, v35
	v_pk_mul_f32 v[2:3], v[4:5], v[2:3]
	v_bfe_u32 v14, v7, 16, 1
	v_bfe_u32 v4, v3, 16, 1
	v_bfe_u32 v5, v2, 16, 1
	v_bfe_u32 v15, v6, 16, 1
	v_add3_u32 v6, v6, v15, s33
	v_add3_u32 v7, v7, v14, s33
	v_add3_u32 v2, v2, v5, s33
	v_add3_u32 v3, v3, v4, s33
	v_bfe_u32 v4, v20, 16, 1
	v_bfe_u32 v5, v21, 16, 1
	v_bfe_u32 v14, v8, 16, 1
	v_bfe_u32 v15, v9, 16, 1
	v_add3_u32 v9, v9, v15, s33
	v_add3_u32 v8, v8, v14, s33
	v_add3_u32 v5, v21, v5, s33
	v_add3_u32 v4, v20, v4, s33
	v_lshrrev_b32_e32 v14, 16, v4
	v_lshrrev_b32_e32 v15, 16, v5
	v_lshrrev_b32_e32 v4, 16, v8
	v_lshrrev_b32_e32 v5, 16, v9
	v_and_or_b32 v5, v3, s34, v5
	v_and_or_b32 v4, v2, s34, v4
	v_and_or_b32 v3, v7, s34, v15
	v_and_or_b32 v2, v6, s34, v14
	v_lshlrev_b64 v[6:7], 11, v[60:61]
	v_lshl_add_u64 v[6:7], s[68:69], 0, v[6:7]
	v_lshl_add_u64 v[6:7], v[6:7], 0, s[70:71]
	v_lshl_add_u64 v[6:7], v[6:7], 0, v[42:43]
	v_lshl_add_u64 v[8:9], v[6:7], 0, s[74:75]
	v_add_co_u32_e32 v6, vcc, 0xdc00000, v6
	s_nop 1
	v_addc_co_u32_e32 v7, vcc, 0, v7, vcc
	global_store_dwordx4 v[6:7], v[10:13], off offset:1024
	global_store_dwordx4 v[8:9], v[2:5], off offset:16
	s_branch .LBB0_5556

.LBB0_5691:
	s_or_b64 exec, exec, s[10:11]
	v_mov_b32_e32 v1, v0
	v_mov_b64_e32 v[2:3], s[0:1]
	s_barrier
	global_load_dwordx2 v[2:3], v[2:3], off offset:88 sc0 sc1
	s_waitcnt vmcnt(0)
	v_readfirstlane_b32 s5, v1
	s_ashr_i32 s5, s5, 4
	s_and_b32 s6, s5, -4
	s_cmp_gt_i32 s6, 63
	s_cbranch_scc1 .LBB0_5694
	v_and_b32_e32 v21, 63, v1
	v_mov_b32_e32 v91, 0
	v_lshlrev_b32_e32 v90, 4, v21
	s_waitcnt lgkmcnt(0)
	v_lshl_add_u64 v[2:3], v[2:3], 0, v[90:91]
	s_movk_i32 s5, 0x5000
	v_add_co_u32_e32 v18, vcc, s5, v2
	v_mbcnt_lo_u32_b32 v1, -1, 0
	s_nop 0
	v_addc_co_u32_e32 v19, vcc, 0, v3, vcc
	global_load_dwordx4 v[2:5], v[18:19], off
	global_load_dwordx4 v[6:9], v[18:19], off offset:1024
	global_load_dwordx4 v[10:13], v[18:19], off offset:2048
	global_load_dwordx4 v[14:17], v[18:19], off offset:3072
	v_mbcnt_hi_u32_b32 v18, -1, v1
	v_and_b32_e32 v1, 64, v18
	v_add_u32_e32 v19, 64, v1
	v_xor_b32_e32 v1, 1, v18
	v_cmp_lt_i32_e32 vcc, v1, v19
	v_xor_b32_e32 v20, 2, v18
	s_lshl_b32 s7, s28, 8
	v_cndmask_b32_e32 v1, v18, v1, vcc
	v_cmp_lt_i32_e32 vcc, v20, v19
	s_lshl_b32 s4, s4, 6
	s_add_i32 s8, s7, s4
	v_cndmask_b32_e32 v20, v18, v20, vcc
	v_lshlrev_b32_e32 v166, 2, v20
	v_xor_b32_e32 v20, 4, v18
	v_cmp_lt_i32_e32 vcc, v20, v19
	s_add_i32 s10, s6, s8
	s_add_u32 s4, s68, 0x5800000
	v_cndmask_b32_e32 v20, v18, v20, vcc
	v_lshlrev_b32_e32 v167, 2, v20
	v_xor_b32_e32 v20, 8, v18
	v_cmp_lt_i32_e32 vcc, v20, v19
	s_addc_u32 s5, s69, 0
	s_lshl_b32 s3, s3, 6
	v_cndmask_b32_e32 v20, v18, v20, vcc
	v_lshlrev_b32_e32 v168, 2, v20
	v_xor_b32_e32 v20, 16, v18
	v_cmp_lt_i32_e32 vcc, v20, v19
	s_add_i32 s3, s7, s3
	s_add_i32 s3, s3, s6
	v_cndmask_b32_e32 v20, v18, v20, vcc
	v_lshlrev_b32_e32 v169, 2, v20
	v_xor_b32_e32 v20, 32, v18
	v_cmp_lt_i32_e32 vcc, v20, v19
	s_lshl_b32 s2, s2, 6
	s_sub_i32 s2, s3, s2
	v_cndmask_b32_e32 v18, v18, v20, vcc
	s_ashr_i32 s11, s10, 31
	v_lshlrev_b32_e32 v170, 2, v18
	v_lshlrev_b32_e32 v18, 2, v21
	s_or_b32 s20, s8, 32
	s_sub_i32 s8, s2, 32
	s_lshl_b64 s[2:3], s[10:11], 11
	v_or_b32_e32 v20, 0x100, v18
	v_or_b32_e32 v22, 0x200, v18
	v_or_b32_e32 v24, 0x300, v18
	v_lshl_or_b32 v92, v21, 3, s2
	v_mov_b32_e32 v93, s3
	s_lshl_b64 s[2:3], s[10:11], 12
	v_lshlrev_b32_e32 v1, 2, v1
	v_or_b32_e32 v94, s2, v90
	v_mov_b32_e32 v95, s3
	v_mov_b32_e32 v171, 0x358637bd
	s_mov_b32 s2, 0xf800000
	v_mov_b32_e32 v172, 0x260
	v_lshlrev_b32_e32 v90, 2, v18
	s_movk_i32 s3, 0x7fff
	s_mov_b32 s21, 0xffff0000
	s_mov_b32 s22, 0xba00000
	v_lshlrev_b32_e32 v96, 2, v20
	v_lshlrev_b32_e32 v98, 2, v22
	v_mov_b32_e32 v99, v91
	v_lshlrev_b32_e32 v100, 2, v24
	v_mov_b32_e32 v101, v91
	s_mov_b32 s23, 0xba01000
	s_mov_b64 s[12:13], 0x10000
	s_mov_b64 s[14:15], 0x20000
	v_mov_b32_e32 v97, v91
.LBB0_5693:
	v_lshl_add_u64 v[18:19], s[68:69], 0, v[94:95]
	v_lshl_add_u64 v[22:23], s[68:69], 0, v[92:93]
	v_add_co_u32_e32 v20, vcc, 0x7800000, v18
	v_add_co_u32_e64 v102, s[6:7], s22, v22
	s_nop 0
	v_addc_co_u32_e32 v21, vcc, 0, v19, vcc
	v_addc_co_u32_e64 v103, s[6:7], 0, v23, s[6:7]
	v_add_co_u32_e64 v104, s[6:7], s23, v22
	v_add_co_u32_e32 v22, vcc, 0x7801000, v18
	s_nop 0
	v_addc_co_u32_e64 v105, s[6:7], 0, v23, s[6:7]
	global_load_dwordx4 v[78:81], v[20:21], off
	global_load_dwordx4 v[74:77], v[20:21], off offset:1024
	global_load_dwordx4 v[70:73], v[20:21], off offset:2048
	global_load_dwordx4 v[66:69], v[20:21], off offset:3072
	v_addc_co_u32_e32 v23, vcc, 0, v19, vcc
	v_add_co_u32_e32 v20, vcc, 0x7802000, v18
	global_load_dwordx4 v[62:65], v[22:23], off
	global_load_dwordx4 v[58:61], v[22:23], off offset:1024
	global_load_dwordx4 v[54:57], v[22:23], off offset:2048
	global_load_dwordx4 v[50:53], v[22:23], off offset:3072
	v_addc_co_u32_e32 v21, vcc, 0, v19, vcc
	v_add_co_u32_e32 v82, vcc, 0x7803000, v18
	global_load_dwordx4 v[46:49], v[20:21], off
	global_load_dwordx4 v[42:45], v[20:21], off offset:1024
	global_load_dwordx4 v[38:41], v[20:21], off offset:2048
	global_load_dwordx4 v[34:37], v[20:21], off offset:3072
	v_addc_co_u32_e32 v83, vcc, 0, v19, vcc
	global_load_dwordx4 v[30:33], v[82:83], off
	global_load_dwordx4 v[26:29], v[82:83], off offset:1024
	global_load_dwordx4 v[22:25], v[82:83], off offset:2048
	global_load_dwordx4 v[18:21], v[82:83], off offset:3072
	s_add_i32 s24, s8, 32
	s_add_i32 s10, s8, 0xffffc022
	s_ashr_i32 s9, s24, 13
	s_cmpk_lt_i32 s24, 0x4000
	s_cselect_b32 s6, s9, s10
	s_addk_i32 s6, 0x82
	s_mul_hi_i32 s7, s6, 0x9000
	s_mul_i32 s6, s6, 0x9000
	s_add_u32 s10, s4, s6
	s_addc_u32 s11, s5, s7
	s_add_u32 s6, s10, 0x6000
	s_addc_u32 s7, s11, 0
	s_add_u32 s10, s10, 0x7000
	s_addc_u32 s11, s11, 0
	v_lshl_add_u64 v[82:83], s[6:7], 0, v[90:91]
	v_lshl_add_u64 v[86:87], s[10:11], 0, v[90:91]
	global_load_dwordx4 v[82:85], v[82:83], off
	v_lshl_add_u64 v[148:149], s[6:7], 0, v[96:97]
	global_load_dwordx4 v[86:89], v[86:87], off
	v_lshl_add_u64 v[142:143], s[6:7], 0, v[98:99]
	v_lshl_add_u64 v[132:133], s[6:7], 0, v[100:101]
	s_add_i32 s6, s8, 0xffffc023
	s_cmpk_lt_i32 s24, 0x3fff
	s_cselect_b32 s6, s9, s6
	s_addk_i32 s6, 0x82
	s_mul_hi_i32 s7, s6, 0x9000
	s_mul_i32 s6, s6, 0x9000
	v_lshl_add_u64 v[152:153], s[10:11], 0, v[96:97]
	v_lshl_add_u64 v[146:147], s[10:11], 0, v[98:99]
	v_lshl_add_u64 v[140:141], s[10:11], 0, v[100:101]
	s_add_u32 s10, s4, s6
	s_addc_u32 s11, s5, s7
	s_add_u32 s6, s10, 0x6000
	s_addc_u32 s7, s11, 0
	s_add_u32 s10, s10, 0x7000
	v_lshl_add_u64 v[134:135], s[6:7], 0, v[90:91]
	v_lshl_add_u64 v[126:127], s[6:7], 0, v[96:97]
	v_lshl_add_u64 v[118:119], s[6:7], 0, v[98:99]
	v_lshl_add_u64 v[114:115], s[6:7], 0, v[100:101]
	s_addc_u32 s11, s11, 0
	s_add_i32 s6, s8, 0xffffc024
	s_cmpk_lt_i32 s24, 0x3ffe
	s_cselect_b32 s6, s9, s6
	s_addk_i32 s6, 0x82
	s_mul_hi_i32 s7, s6, 0x9000
	s_mul_i32 s6, s6, 0x9000
	s_add_u32 s6, s4, s6
	s_addc_u32 s7, s5, s7
	v_lshl_add_u64 v[136:137], s[10:11], 0, v[90:91]
	v_lshl_add_u64 v[130:131], s[10:11], 0, v[96:97]
	v_lshl_add_u64 v[122:123], s[10:11], 0, v[98:99]
	v_lshl_add_u64 v[116:117], s[10:11], 0, v[100:101]
	s_add_u32 s10, s6, 0x6000
	s_addc_u32 s11, s7, 0
	s_add_u32 s6, s6, 0x7000
	s_addc_u32 s7, s7, 0
	s_addk_i32 s8, 0xc025
	s_cmpk_lt_i32 s24, 0x3ffd
	v_lshl_add_u64 v[156:157], s[6:7], 0, v[90:91]
	v_lshl_add_u64 v[154:155], s[6:7], 0, v[96:97]
	v_lshl_add_u64 v[150:151], s[6:7], 0, v[98:99]
	v_lshl_add_u64 v[138:139], s[6:7], 0, v[100:101]
	s_cselect_b32 s6, s9, s8
	s_waitcnt vmcnt(0) lgkmcnt(0)
	v_pk_mul_f32 v[158:159], v[80:81], v[80:81]
	v_pk_mul_f32 v[160:161], v[78:79], v[78:79]
	v_pk_mul_f32 v[162:163], v[76:77], v[76:77]
	v_pk_mul_f32 v[164:165], v[74:75], v[74:75]
	v_mul_f32_e32 v174, v71, v71
	v_mul_f32_e32 v176, v73, v73
	v_mul_f32_e32 v187, v68, v68
	v_mul_f32_e32 v189, v69, v69
	v_pk_mov_b32 v[178:179], v[160:161], v[158:159] op_sel:[1,0]
	v_mov_b32_e32 v161, v159
	v_pk_mov_b32 v[158:159], v[164:165], v[162:163] op_sel:[1,0]
	v_mov_b32_e32 v165, v163
	v_pk_fma_f32 v[162:163], v[70:71], v[70:71], v[174:175] op_sel_hi:[1,1,0]
	v_pk_fma_f32 v[174:175], v[72:73], v[72:73], v[176:177] op_sel_hi:[1,1,0]
	v_pk_mul_f32 v[176:177], v[64:65], v[64:65]
	v_pk_mul_f32 v[180:181], v[62:63], v[62:63]
	v_pk_mul_f32 v[182:183], v[60:61], v[60:61]
	v_pk_mul_f32 v[184:185], v[58:59], v[58:59]
	v_mul_f32_e32 v186, v55, v55
	v_mul_f32_e32 v188, v57, v57
	v_pk_add_f32 v[160:161], v[178:179], v[160:161]
	v_pk_add_f32 v[158:159], v[158:159], v[164:165]
	v_mov_b32_e32 v163, v187
	v_mov_b32_e32 v175, v189
	v_pk_mov_b32 v[164:165], v[180:181], v[176:177] op_sel:[1,0]
	v_mov_b32_e32 v181, v177
	v_pk_mov_b32 v[176:177], v[184:185], v[182:183] op_sel:[1,0]
	v_mov_b32_e32 v185, v183
	v_pk_fma_f32 v[178:179], v[54:55], v[54:55], v[186:187] op_sel_hi:[1,1,0]
	v_pk_fma_f32 v[182:183], v[56:57], v[56:57], v[188:189] op_sel_hi:[1,1,0]
	v_pk_mul_f32 v[186:187], v[48:49], v[48:49]
	v_pk_mul_f32 v[188:189], v[46:47], v[46:47]
	v_pk_mul_f32 v[190:191], v[44:45], v[44:45]
	v_pk_mul_f32 v[192:193], v[42:43], v[42:43]
	v_mul_f32_e32 v173, v66, v66
	v_mul_f32_e32 v197, v67, v67
	v_mul_f32_e32 v195, v52, v52
	v_mul_f32_e32 v202, v53, v53
	v_mul_f32_e32 v194, v39, v39
	v_mul_f32_e32 v196, v41, v41
	v_pk_add_f32 v[198:199], v[160:161], v[160:161] op_sel:[0,1] op_sel_hi:[1,0]
	v_pk_add_f32 v[200:201], v[158:159], v[158:159] op_sel:[0,1] op_sel_hi:[1,0]
	v_pk_add_f32 v[174:175], v[162:163], v[174:175]
	v_pk_add_f32 v[158:159], v[164:165], v[180:181]
	v_pk_add_f32 v[160:161], v[176:177], v[184:185]
	v_pk_mov_b32 v[162:163], v[188:189], v[186:187] op_sel:[1,0]
	v_mov_b32_e32 v189, v187
	v_pk_mov_b32 v[164:165], v[192:193], v[190:191] op_sel:[1,0]
	v_mov_b32_e32 v193, v191
	v_mul_f32_e32 v203, v50, v50
	v_mul_f32_e32 v208, v51, v51
	v_mul_f32_e32 v211, v36, v36
	v_mul_f32_e32 v212, v37, v37
	v_mov_b32_e32 v179, v195
	v_mov_b32_e32 v183, v202
	v_pk_fma_f32 v[176:177], v[38:39], v[38:39], v[194:195] op_sel_hi:[1,1,0]
	v_pk_fma_f32 v[180:181], v[40:41], v[40:41], v[196:197] op_sel_hi:[1,1,0]
	v_pk_mul_f32 v[184:185], v[32:33], v[32:33]
	v_pk_mul_f32 v[186:187], v[30:31], v[30:31]
	v_pk_mul_f32 v[190:191], v[28:29], v[28:29]
	v_pk_mul_f32 v[194:195], v[26:27], v[26:27]
	v_mov_b32_e32 v199, v173
	v_mov_b32_e32 v201, v197
	v_pk_add_f32 v[204:205], v[158:159], v[158:159] op_sel:[0,1] op_sel_hi:[1,0]
	v_pk_add_f32 v[206:207], v[160:161], v[160:161] op_sel:[0,1] op_sel_hi:[1,0]
	v_pk_add_f32 v[162:163], v[162:163], v[188:189]
	v_pk_add_f32 v[164:165], v[164:165], v[192:193]
	v_mul_f32_e32 v209, v34, v34
	v_mul_f32_e32 v210, v35, v35
	v_pk_add_f32 v[178:179], v[178:179], v[182:183]
	v_mov_b32_e32 v177, v211
	v_mov_b32_e32 v181, v212
	v_pk_mov_b32 v[182:183], v[186:187], v[184:185] op_sel:[1,0]
	v_mov_b32_e32 v187, v185
	v_pk_mov_b32 v[184:185], v[194:195], v[190:191] op_sel:[1,0]
	v_mov_b32_e32 v195, v191
	v_pk_add_f32 v[188:189], v[198:199], v[200:201]
	v_mov_b32_e32 v205, v203
	v_mov_b32_e32 v207, v208
	v_pk_add_f32 v[190:191], v[162:163], v[162:163] op_sel:[0,1] op_sel_hi:[1,0]
	v_pk_add_f32 v[192:193], v[164:165], v[164:165] op_sel:[0,1] op_sel_hi:[1,0]
	v_pk_add_f32 v[176:177], v[176:177], v[180:181]
	v_pk_add_f32 v[174:175], v[188:189], v[174:175]
	v_pk_add_f32 v[180:181], v[204:205], v[206:207]
	v_mov_b32_e32 v191, v209
	v_mov_b32_e32 v193, v210
	v_add_f32_e32 v173, v174, v175
	v_pk_add_f32 v[174:175], v[180:181], v[178:179]
	v_pk_add_f32 v[178:179], v[190:191], v[192:193]
	v_add_f32_e32 v180, v174, v175
	v_pk_add_f32 v[174:175], v[178:179], v[176:177]
	ds_bpermute_b32 v176, v1, v173
	v_add_f32_e32 v174, v174, v175
	ds_bpermute_b32 v175, v1, v180
	ds_bpermute_b32 v177, v1, v174
	s_addk_i32 s6, 0x82
	s_waitcnt lgkmcnt(2)
	v_add_f32_e32 v173, v173, v176
	ds_bpermute_b32 v176, v166, v173
	s_waitcnt lgkmcnt(2)
	v_add_f32_e32 v175, v180, v175
	ds_bpermute_b32 v178, v166, v175
	s_waitcnt lgkmcnt(2)
	v_add_f32_e32 v174, v174, v177
	ds_bpermute_b32 v177, v166, v174
	s_waitcnt lgkmcnt(2)
	v_add_f32_e32 v173, v173, v176
	ds_bpermute_b32 v176, v167, v173
	s_waitcnt lgkmcnt(2)
	v_add_f32_e32 v175, v175, v178
	ds_bpermute_b32 v178, v167, v175
	s_waitcnt lgkmcnt(2)
	v_add_f32_e32 v174, v174, v177
	ds_bpermute_b32 v177, v167, v174
	s_waitcnt lgkmcnt(2)
	v_add_f32_e32 v173, v173, v176
	ds_bpermute_b32 v176, v168, v173
	s_waitcnt lgkmcnt(2)
	v_add_f32_e32 v175, v175, v178
	ds_bpermute_b32 v178, v168, v175
	s_waitcnt lgkmcnt(2)
	v_add_f32_e32 v174, v174, v177
	ds_bpermute_b32 v177, v168, v174
	s_waitcnt lgkmcnt(2)
	v_add_f32_e32 v173, v173, v176
	ds_bpermute_b32 v176, v169, v173
	s_waitcnt lgkmcnt(2)
	v_add_f32_e32 v175, v175, v178
	ds_bpermute_b32 v178, v169, v175
	s_waitcnt lgkmcnt(2)
	v_add_f32_e32 v174, v174, v177
	ds_bpermute_b32 v177, v169, v174
	s_waitcnt lgkmcnt(2)
	v_add_f32_e32 v173, v173, v176
	ds_bpermute_b32 v176, v170, v173
	s_waitcnt lgkmcnt(2)
	v_add_f32_e32 v175, v175, v178
	ds_bpermute_b32 v178, v170, v175
	s_mul_hi_i32 s7, s6, 0x9000
	s_mul_i32 s6, s6, 0x9000
	s_waitcnt lgkmcnt(2)
	v_add_f32_e32 v174, v174, v177
	s_add_u32 s6, s4, s6
	ds_bpermute_b32 v177, v170, v174
	s_addc_u32 s7, s5, s7
	s_waitcnt lgkmcnt(2)
	v_add_f32_e32 v173, v173, v176
	s_add_u32 s16, s6, 0x6000
	v_fmamk_f32 v173, v173, 0x3a800000, v171
	s_addc_u32 s17, s7, 0
	s_waitcnt lgkmcnt(1)
	v_add_f32_e32 v175, v175, v178
	v_mul_f32_e32 v176, 0x4f800000, v173
	v_cmp_gt_f32_e32 vcc, s2, v173
	s_add_u32 s18, s6, 0x7000
	v_fmamk_f32 v175, v175, 0x3a800000, v171
	v_cndmask_b32_e32 v173, v173, v176, vcc
	s_addc_u32 s19, s7, 0
	s_waitcnt lgkmcnt(0)
	v_add_f32_e32 v174, v174, v177
	v_mul_f32_e32 v176, 0x4f800000, v175
	v_cmp_gt_f32_e64 s[6:7], s2, v175
	v_sqrt_f32_e32 v177, v173
	v_fmamk_f32 v174, v174, 0x3a800000, v171
	v_cndmask_b32_e64 v175, v175, v176, s[6:7]
	v_mul_f32_e32 v176, 0x4f800000, v174
	v_cmp_gt_f32_e64 s[8:9], s2, v174
	v_sqrt_f32_e32 v178, v175
	v_add_u32_e32 v179, -1, v177
	v_cndmask_b32_e64 v174, v174, v176, s[8:9]
	v_sqrt_f32_e32 v176, v174
	v_add_u32_e32 v180, 1, v177
	v_fma_f32 v181, -v179, v177, v173
	v_lshl_add_u64 v[112:113], s[10:11], 0, v[90:91]
	v_lshl_add_u64 v[106:107], s[10:11], 0, v[96:97]
	v_lshl_add_u64 v[110:111], s[10:11], 0, v[98:99]
	v_lshl_add_u64 v[108:109], s[10:11], 0, v[100:101]
	v_pk_add_f32 v[162:163], v[182:183], v[186:187]
	v_fma_f32 v182, -v180, v177, v173
	v_add_u32_e32 v183, -1, v178
	v_cmp_ge_f32_e64 s[10:11], 0, v181
	v_pk_add_f32 v[164:165], v[184:185], v[194:195]
	v_add_u32_e32 v184, 1, v178
	v_cndmask_b32_e64 v177, v177, v179, s[10:11]
	v_fma_f32 v179, -v183, v178, v175
	v_cmp_lt_f32_e64 s[10:11], 0, v182
	v_fma_f32 v181, -v184, v178, v175
	v_add_u32_e32 v185, -1, v176
	v_cndmask_b32_e64 v177, v177, v180, s[10:11]
	v_cmp_ge_f32_e64 s[10:11], 0, v179
	v_add_u32_e32 v186, 1, v176
	v_fma_f32 v179, -v185, v176, v174
	v_cndmask_b32_e64 v178, v178, v183, s[10:11]
	v_cmp_lt_f32_e64 s[10:11], 0, v181
	v_fma_f32 v180, -v186, v176, v174
	v_mul_f32_e32 v181, 0x37800000, v177
	v_cndmask_b32_e64 v178, v178, v184, s[10:11]
	v_cmp_ge_f32_e64 s[10:11], 0, v179
	v_cndmask_b32_e32 v177, v177, v181, vcc
	v_cmp_class_f32_e32 vcc, v173, v172
	v_cndmask_b32_e64 v176, v176, v185, s[10:11]
	v_cmp_lt_f32_e64 s[10:11], 0, v180
	v_mul_f32_e32 v179, 0x37800000, v178
	v_cndmask_b32_e32 v173, v177, v173, vcc
	v_cndmask_b32_e64 v176, v176, v186, s[10:11]
	v_cndmask_b32_e64 v177, v178, v179, s[6:7]
	v_cmp_class_f32_e32 vcc, v175, v172
	v_mul_f32_e32 v178, 0x37800000, v176
	v_div_scale_f32 v179, s[6:7], v173, v173, 1.0
	v_cndmask_b32_e32 v175, v177, v175, vcc
	v_cndmask_b32_e64 v176, v176, v178, s[8:9]
	v_cmp_class_f32_e32 vcc, v174, v172
	v_rcp_f32_e32 v177, v179
	v_div_scale_f32 v178, s[8:9], v175, v175, 1.0
	v_cndmask_b32_e32 v176, v176, v174, vcc
	v_rcp_f32_e32 v182, v178
	v_div_scale_f32 v183, s[10:11], v176, v176, 1.0
	v_rcp_f32_e32 v185, v183
	v_fma_f32 v174, -v179, v177, 1.0
	v_div_scale_f32 v180, s[6:7], 1.0, v173, 1.0
	v_fmac_f32_e32 v177, v174, v177
	v_fma_f32 v174, -v178, v182, 1.0
	v_mul_f32_e32 v186, v180, v177
	v_div_scale_f32 v181, s[8:9], 1.0, v175, 1.0
	v_fmac_f32_e32 v182, v174, v182
	v_fma_f32 v174, -v183, v185, 1.0
	v_fma_f32 v187, -v179, v186, v180
	v_div_scale_f32 v184, s[10:11], 1.0, v176, 1.0
	v_mul_f32_e32 v188, v181, v182
	v_fmac_f32_e32 v185, v174, v185
	v_fmac_f32_e32 v186, v187, v177
	v_fma_f32 v174, -v178, v188, v181
	v_mul_f32_e32 v187, v184, v185
	v_fma_f32 v179, -v179, v186, v180
	s_mov_b64 vcc, s[6:7]
	v_fmac_f32_e32 v188, v174, v182
	v_fma_f32 v174, -v183, v187, v184
	v_div_fmas_f32 v177, v179, v177, v186
	v_fma_f32 v178, -v178, v188, v181
	v_fmac_f32_e32 v187, v174, v185
	v_div_fixup_f32 v174, v177, v173, 1.0
	s_mov_b64 vcc, s[8:9]
	v_div_fmas_f32 v173, v178, v182, v188
	v_fma_f32 v177, -v183, v187, v184
	v_pk_mul_f32 v[80:81], v[80:81], v[174:175] op_sel_hi:[1,0]
	v_pk_mul_f32 v[78:79], v[78:79], v[174:175] op_sel_hi:[1,0]
	s_mov_b64 vcc, s[10:11]
	v_pk_add_f32 v[88:89], v[88:89], 1.0 op_sel_hi:[1,0]
	v_pk_add_f32 v[86:87], v[86:87], 1.0 op_sel_hi:[1,0]
	v_pk_mul_f32 v[76:77], v[76:77], v[174:175] op_sel_hi:[1,0]
	v_pk_mul_f32 v[74:75], v[74:75], v[174:175] op_sel_hi:[1,0]
	v_pk_mul_f32 v[72:73], v[72:73], v[174:175] op_sel_hi:[1,0]
	v_pk_mul_f32 v[70:71], v[70:71], v[174:175] op_sel_hi:[1,0]
	v_pk_mul_f32 v[68:69], v[68:69], v[174:175] op_sel_hi:[1,0]
	v_pk_mul_f32 v[66:67], v[66:67], v[174:175] op_sel_hi:[1,0]
	v_div_fixup_f32 v174, v173, v175, 1.0
	v_div_fmas_f32 v173, v177, v185, v187
	v_pk_mul_f32 v[78:79], v[2:3], v[78:79]
	v_pk_mul_f32 v[80:81], v[4:5], v[80:81]
	v_pk_mul_f32 v[64:65], v[64:65], v[174:175] op_sel_hi:[1,0]
	v_pk_mul_f32 v[62:63], v[62:63], v[174:175] op_sel_hi:[1,0]
	v_pk_mul_f32 v[60:61], v[60:61], v[174:175] op_sel_hi:[1,0]
	v_pk_mul_f32 v[58:59], v[58:59], v[174:175] op_sel_hi:[1,0]
	v_pk_mul_f32 v[56:57], v[56:57], v[174:175] op_sel_hi:[1,0]
	v_pk_mul_f32 v[54:55], v[54:55], v[174:175] op_sel_hi:[1,0]
	v_pk_mul_f32 v[52:53], v[52:53], v[174:175] op_sel_hi:[1,0]
	v_pk_mul_f32 v[174:175], v[50:51], v[174:175] op_sel_hi:[1,0]
	v_div_fixup_f32 v50, v173, v176, 1.0
	v_pk_fma_f32 v[80:81], v[88:89], v[80:81], v[84:85]
	v_pk_fma_f32 v[78:79], v[86:87], v[78:79], v[82:83]
	v_pk_mul_f32 v[86:87], v[16:17], v[52:53]
	v_pk_mul_f32 v[48:49], v[48:49], v[50:51] op_sel_hi:[1,0]
	v_pk_mul_f32 v[46:47], v[46:47], v[50:51] op_sel_hi:[1,0]
	v_bfe_u32 v51, v78, 16, 1
	v_bfe_u32 v53, v80, 16, 1
	v_pk_mul_f32 v[82:83], v[10:11], v[54:55]
	v_pk_mul_f32 v[84:85], v[14:15], v[174:175]
	v_bfe_u32 v52, v79, 16, 1
	v_bfe_u32 v54, v81, 16, 1
	v_pk_mul_f32 v[88:89], v[2:3], v[46:47]
	v_pk_mul_f32 v[174:175], v[4:5], v[48:49]
	v_add3_u32 v46, v78, v51, s3
	v_add3_u32 v48, v80, v53, s3
	v_add3_u32 v47, v79, v52, s3
	v_add3_u32 v49, v81, v54, s3
	v_lshrrev_b32_e32 v46, 16, v46
	v_lshrrev_b32_e32 v48, 16, v48
	v_and_or_b32 v46, v47, s21, v46
	v_and_or_b32 v47, v49, s21, v48
	global_store_dwordx2 v[102:103], v[46:47], off
	global_load_dwordx4 v[46:49], v[152:153], off
	s_nop 0
	global_load_dwordx4 v[52:55], v[148:149], off
	v_pk_mul_f32 v[74:75], v[6:7], v[74:75]
	v_pk_mul_f32 v[76:77], v[8:9], v[76:77]
	v_pk_mul_f32 v[70:71], v[10:11], v[70:71]
	v_pk_mul_f32 v[72:73], v[12:13], v[72:73]
	v_pk_mul_f32 v[66:67], v[66:67], v[14:15]
	v_pk_mul_f32 v[68:69], v[68:69], v[16:17]
	v_pk_mul_f32 v[62:63], v[2:3], v[62:63]
	v_pk_mul_f32 v[64:65], v[4:5], v[64:65]
	v_pk_mul_f32 v[58:59], v[6:7], v[58:59]
	v_pk_mul_f32 v[60:61], v[8:9], v[60:61]
	v_pk_mul_f32 v[56:57], v[12:13], v[56:57]
	v_mul_f32_e32 v196, v23, v23
	v_mul_f32_e32 v202, v25, v25
	v_mul_f32_e32 v213, v18, v18
	v_mul_f32_e32 v214, v19, v19
	v_mul_f32_e32 v215, v20, v20
	v_mul_f32_e32 v216, v21, v21
	v_pk_fma_f32 v[158:159], v[22:23], v[22:23], v[196:197] op_sel_hi:[1,1,0]
	v_pk_fma_f32 v[160:161], v[24:25], v[24:25], v[202:203] op_sel_hi:[1,1,0]
	v_mov_b32_e32 v159, v215
	v_mov_b32_e32 v161, v216
	v_lshl_add_u64 v[144:145], s[18:19], 0, v[90:91]
	v_lshl_add_u64 v[128:129], s[16:17], 0, v[90:91]
	v_lshl_add_u64 v[124:125], s[18:19], 0, v[96:97]
	v_lshl_add_u64 v[120:121], s[16:17], 0, v[96:97]
	v_lshl_add_u64 v[92:93], v[92:93], 0, s[12:13]
	v_lshl_add_u64 v[94:95], v[94:95], 0, s[14:15]
	s_mov_b32 s8, s24
	s_cmp_lt_i32 s24, s20
	s_waitcnt vmcnt(0) lgkmcnt(0)
	v_pk_add_f32 v[48:49], v[48:49], 1.0 op_sel_hi:[1,0]
	v_pk_add_f32 v[46:47], v[46:47], 1.0 op_sel_hi:[1,0]
	v_pk_fma_f32 v[48:49], v[48:49], v[76:77], v[54:55]
	v_pk_fma_f32 v[46:47], v[46:47], v[74:75], v[52:53]
	v_bfe_u32 v53, v48, 16, 1
	v_bfe_u32 v51, v46, 16, 1
	v_bfe_u32 v52, v47, 16, 1
	v_bfe_u32 v54, v49, 16, 1
	v_add3_u32 v46, v46, v51, s3
	v_add3_u32 v48, v48, v53, s3
	v_add3_u32 v47, v47, v52, s3
	v_add3_u32 v49, v49, v54, s3
	v_lshrrev_b32_e32 v46, 16, v46
	v_lshrrev_b32_e32 v48, 16, v48
	v_and_or_b32 v46, v47, s21, v46
	v_and_or_b32 v47, v49, s21, v48
	global_store_dwordx2 v[102:103], v[46:47], off offset:512
	global_load_dwordx4 v[46:49], v[146:147], off
	s_nop 0
	global_load_dwordx4 v[52:55], v[142:143], off
	s_waitcnt vmcnt(0) lgkmcnt(0)
	v_pk_add_f32 v[48:49], v[48:49], 1.0 op_sel_hi:[1,0]
	v_pk_add_f32 v[46:47], v[46:47], 1.0 op_sel_hi:[1,0]
	v_pk_fma_f32 v[48:49], v[72:73], v[48:49], v[54:55]
	v_pk_fma_f32 v[46:47], v[70:71], v[46:47], v[52:53]
	v_bfe_u32 v53, v48, 16, 1
	v_bfe_u32 v51, v46, 16, 1
	v_bfe_u32 v52, v47, 16, 1
	v_bfe_u32 v54, v49, 16, 1
	v_add3_u32 v46, v46, v51, s3
	v_add3_u32 v48, v48, v53, s3
	v_add3_u32 v47, v47, v52, s3
	v_add3_u32 v49, v49, v54, s3
	v_lshrrev_b32_e32 v46, 16, v46
	v_lshrrev_b32_e32 v48, 16, v48
	v_and_or_b32 v46, v47, s21, v46
	v_and_or_b32 v47, v49, s21, v48
	global_store_dwordx2 v[102:103], v[46:47], off offset:1024
	global_load_dwordx4 v[46:49], v[140:141], off
	s_nop 0
	global_load_dwordx4 v[52:55], v[132:133], off
	s_waitcnt vmcnt(0) lgkmcnt(0)
	v_pk_add_f32 v[48:49], v[48:49], 1.0 op_sel_hi:[1,0]
	v_pk_add_f32 v[46:47], v[46:47], 1.0 op_sel_hi:[1,0]
	v_pk_fma_f32 v[48:49], v[68:69], v[48:49], v[54:55]
	v_pk_fma_f32 v[46:47], v[66:67], v[46:47], v[52:53]
	v_bfe_u32 v53, v48, 16, 1
	v_bfe_u32 v51, v46, 16, 1
	v_bfe_u32 v52, v47, 16, 1
	v_bfe_u32 v54, v49, 16, 1
	v_add3_u32 v46, v46, v51, s3
	v_add3_u32 v48, v48, v53, s3
	v_add3_u32 v47, v47, v52, s3
	v_add3_u32 v49, v49, v54, s3
	v_lshrrev_b32_e32 v46, 16, v46
	v_lshrrev_b32_e32 v48, 16, v48
	v_and_or_b32 v46, v47, s21, v46
	v_and_or_b32 v47, v49, s21, v48
	global_store_dwordx2 v[102:103], v[46:47], off offset:1536
	global_load_dwordx4 v[46:49], v[136:137], off
	s_nop 0
	global_load_dwordx4 v[52:55], v[134:135], off
	s_waitcnt vmcnt(0) lgkmcnt(0)
	v_pk_add_f32 v[48:49], v[48:49], 1.0 op_sel_hi:[1,0]
	v_pk_add_f32 v[46:47], v[46:47], 1.0 op_sel_hi:[1,0]
	v_pk_fma_f32 v[48:49], v[48:49], v[64:65], v[54:55]
	v_pk_fma_f32 v[46:47], v[46:47], v[62:63], v[52:53]
	v_bfe_u32 v53, v48, 16, 1
	v_bfe_u32 v51, v46, 16, 1
	v_bfe_u32 v52, v47, 16, 1
	v_bfe_u32 v54, v49, 16, 1
	v_add3_u32 v46, v46, v51, s3
	v_add3_u32 v48, v48, v53, s3
	v_add3_u32 v47, v47, v52, s3
	v_add3_u32 v49, v49, v54, s3
	v_lshrrev_b32_e32 v46, 16, v46
	v_lshrrev_b32_e32 v48, 16, v48
	v_and_or_b32 v46, v47, s21, v46
	v_and_or_b32 v47, v49, s21, v48
	global_store_dwordx2 v[102:103], v[46:47], off offset:2048
	global_load_dwordx4 v[46:49], v[130:131], off
	s_nop 0
	global_load_dwordx4 v[52:55], v[126:127], off
	s_waitcnt vmcnt(0) lgkmcnt(0)
	v_pk_add_f32 v[48:49], v[48:49], 1.0 op_sel_hi:[1,0]
	v_pk_add_f32 v[46:47], v[46:47], 1.0 op_sel_hi:[1,0]
	v_pk_fma_f32 v[48:49], v[48:49], v[60:61], v[54:55]
	v_pk_fma_f32 v[46:47], v[46:47], v[58:59], v[52:53]
	v_bfe_u32 v53, v48, 16, 1
	v_bfe_u32 v51, v46, 16, 1
	v_bfe_u32 v52, v47, 16, 1
	v_bfe_u32 v54, v49, 16, 1
	v_add3_u32 v46, v46, v51, s3
	v_add3_u32 v48, v48, v53, s3
	v_add3_u32 v47, v47, v52, s3
	v_add3_u32 v49, v49, v54, s3
	v_lshrrev_b32_e32 v46, 16, v46
	v_lshrrev_b32_e32 v48, 16, v48
	v_and_or_b32 v46, v47, s21, v46
	v_and_or_b32 v47, v49, s21, v48
	global_store_dwordx2 v[102:103], v[46:47], off offset:2560
	global_load_dwordx4 v[46:49], v[122:123], off
	s_nop 0
	global_load_dwordx4 v[52:55], v[118:119], off
	v_pk_add_f32 v[58:59], v[164:165], v[164:165] op_sel:[0,1] op_sel_hi:[1,0]
	v_pk_add_f32 v[60:61], v[158:159], v[160:161]
	v_mov_b32_e32 v59, v214
	s_waitcnt vmcnt(0) lgkmcnt(0)
	v_pk_add_f32 v[48:49], v[48:49], 1.0 op_sel_hi:[1,0]
	v_pk_add_f32 v[46:47], v[46:47], 1.0 op_sel_hi:[1,0]
	v_pk_fma_f32 v[48:49], v[48:49], v[56:57], v[54:55]
	v_pk_fma_f32 v[46:47], v[46:47], v[82:83], v[52:53]
	v_bfe_u32 v53, v48, 16, 1
	v_bfe_u32 v51, v46, 16, 1
	v_bfe_u32 v52, v47, 16, 1
	v_bfe_u32 v54, v49, 16, 1
	v_add3_u32 v46, v46, v51, s3
	v_add3_u32 v48, v48, v53, s3
	v_add3_u32 v47, v47, v52, s3
	v_add3_u32 v49, v49, v54, s3
	v_lshrrev_b32_e32 v46, 16, v46
	v_lshrrev_b32_e32 v48, 16, v48
	v_and_or_b32 v46, v47, s21, v46
	v_and_or_b32 v47, v49, s21, v48
	global_store_dwordx2 v[102:103], v[46:47], off offset:3072
	global_load_dwordx4 v[46:49], v[116:117], off
	s_nop 0
	global_load_dwordx4 v[52:55], v[114:115], off
	v_pk_add_f32 v[56:57], v[162:163], v[162:163] op_sel:[0,1] op_sel_hi:[1,0]
	s_waitcnt vmcnt(0) lgkmcnt(0)
	v_pk_add_f32 v[48:49], v[48:49], 1.0 op_sel_hi:[1,0]
	v_pk_add_f32 v[46:47], v[46:47], 1.0 op_sel_hi:[1,0]
	v_pk_fma_f32 v[48:49], v[86:87], v[48:49], v[54:55]
	v_pk_fma_f32 v[46:47], v[84:85], v[46:47], v[52:53]
	v_bfe_u32 v53, v48, 16, 1
	v_bfe_u32 v51, v46, 16, 1
	v_bfe_u32 v52, v47, 16, 1
	v_bfe_u32 v54, v49, 16, 1
	v_add3_u32 v46, v46, v51, s3
	v_add3_u32 v48, v48, v53, s3
	v_add3_u32 v47, v47, v52, s3
	v_add3_u32 v49, v49, v54, s3
	v_lshrrev_b32_e32 v46, 16, v46
	v_lshrrev_b32_e32 v48, 16, v48
	v_and_or_b32 v46, v47, s21, v46
	v_and_or_b32 v47, v49, s21, v48
	global_store_dwordx2 v[102:103], v[46:47], off offset:3584
	global_load_dwordx4 v[46:49], v[156:157], off
	s_nop 0
	global_load_dwordx4 v[52:55], v[112:113], off
	v_mov_b32_e32 v57, v213
	s_waitcnt vmcnt(0) lgkmcnt(0)
	v_pk_add_f32 v[48:49], v[48:49], 1.0 op_sel_hi:[1,0]
	v_pk_add_f32 v[46:47], v[46:47], 1.0 op_sel_hi:[1,0]
	v_pk_fma_f32 v[48:49], v[48:49], v[174:175], v[54:55]
	v_pk_fma_f32 v[46:47], v[46:47], v[88:89], v[52:53]
	v_bfe_u32 v53, v48, 16, 1
	v_bfe_u32 v51, v46, 16, 1
	v_bfe_u32 v52, v47, 16, 1
	v_bfe_u32 v54, v49, 16, 1
	v_add3_u32 v46, v46, v51, s3
	v_add3_u32 v48, v48, v53, s3
	v_add3_u32 v47, v47, v52, s3
	v_add3_u32 v49, v49, v54, s3
	v_lshrrev_b32_e32 v46, 16, v46
	v_lshrrev_b32_e32 v48, 16, v48
	v_and_or_b32 v46, v47, s21, v46
	v_and_or_b32 v47, v49, s21, v48
	global_store_dwordx2 v[104:105], v[46:47], off
	global_load_dwordx4 v[46:49], v[154:155], off
	s_nop 0
	global_load_dwordx4 v[52:55], v[106:107], off
	v_pk_mul_f32 v[44:45], v[44:45], v[50:51] op_sel_hi:[1,0]
	v_pk_mul_f32 v[42:43], v[42:43], v[50:51] op_sel_hi:[1,0]
	v_pk_mul_f32 v[44:45], v[8:9], v[44:45]
	v_pk_mul_f32 v[42:43], v[6:7], v[42:43]
	s_waitcnt vmcnt(0) lgkmcnt(0)
	v_pk_add_f32 v[48:49], v[48:49], 1.0 op_sel_hi:[1,0]
	v_pk_add_f32 v[46:47], v[46:47], 1.0 op_sel_hi:[1,0]
	v_pk_fma_f32 v[44:45], v[48:49], v[44:45], v[54:55]
	v_pk_fma_f32 v[42:43], v[46:47], v[42:43], v[52:53]
	v_bfe_u32 v48, v44, 16, 1
	v_bfe_u32 v46, v42, 16, 1
	v_bfe_u32 v47, v43, 16, 1
	v_bfe_u32 v49, v45, 16, 1
	v_add3_u32 v42, v42, v46, s3
	v_add3_u32 v44, v44, v48, s3
	v_add3_u32 v43, v43, v47, s3
	v_add3_u32 v45, v45, v49, s3
	v_lshrrev_b32_e32 v42, 16, v42
	v_lshrrev_b32_e32 v44, 16, v44
	v_and_or_b32 v42, v43, s21, v42
	v_and_or_b32 v43, v45, s21, v44
	global_store_dwordx2 v[104:105], v[42:43], off offset:512
	global_load_dwordx4 v[42:45], v[150:151], off
	s_nop 0
	global_load_dwordx4 v[46:49], v[110:111], off
	v_pk_add_f32 v[52:53], v[56:57], v[58:59]
	s_waitcnt vmcnt(0) lgkmcnt(0)
	v_pk_add_f32 v[44:45], v[44:45], 1.0 op_sel_hi:[1,0]
	v_pk_add_f32 v[52:53], v[52:53], v[60:61]
	v_pk_add_f32 v[42:43], v[42:43], 1.0 op_sel_hi:[1,0]
	v_add_f32_e32 v51, v52, v53
	ds_bpermute_b32 v52, v1, v51
	s_waitcnt lgkmcnt(0)
	v_add_f32_e32 v51, v51, v52
	ds_bpermute_b32 v52, v166, v51
	s_waitcnt lgkmcnt(0)
	v_add_f32_e32 v51, v51, v52
	v_pk_mul_f32 v[40:41], v[40:41], v[50:51] op_sel_hi:[1,0]
	v_pk_mul_f32 v[38:39], v[38:39], v[50:51] op_sel_hi:[1,0]
	v_pk_mul_f32 v[40:41], v[12:13], v[40:41]
	v_pk_mul_f32 v[38:39], v[10:11], v[38:39]
	v_pk_fma_f32 v[40:41], v[44:45], v[40:41], v[48:49]
	v_pk_fma_f32 v[38:39], v[42:43], v[38:39], v[46:47]
	v_bfe_u32 v44, v40, 16, 1
	v_bfe_u32 v42, v38, 16, 1
	v_bfe_u32 v43, v39, 16, 1
	v_bfe_u32 v45, v41, 16, 1
	v_add3_u32 v38, v38, v42, s3
	v_add3_u32 v40, v40, v44, s3
	v_add3_u32 v39, v39, v43, s3
	v_add3_u32 v41, v41, v45, s3
	v_lshrrev_b32_e32 v38, 16, v38
	v_lshrrev_b32_e32 v40, 16, v40
	v_and_or_b32 v38, v39, s21, v38
	v_and_or_b32 v39, v41, s21, v40
	global_store_dwordx2 v[104:105], v[38:39], off offset:1024
	global_load_dwordx4 v[38:41], v[138:139], off
	s_nop 0
	global_load_dwordx4 v[42:45], v[108:109], off
	v_pk_mul_f32 v[36:37], v[36:37], v[50:51] op_sel_hi:[1,0]
	v_pk_mul_f32 v[34:35], v[34:35], v[50:51] op_sel_hi:[1,0]
	v_pk_mul_f32 v[36:37], v[16:17], v[36:37]
	v_pk_mul_f32 v[34:35], v[14:15], v[34:35]
	ds_bpermute_b32 v46, v167, v51
	s_waitcnt lgkmcnt(0)
	v_add_f32_e32 v46, v51, v46
	ds_bpermute_b32 v47, v168, v46
	s_waitcnt lgkmcnt(0)
	v_add_f32_e32 v46, v46, v47
	ds_bpermute_b32 v47, v169, v46
	s_waitcnt lgkmcnt(0)
	v_add_f32_e32 v46, v46, v47
	ds_bpermute_b32 v47, v170, v46
	s_waitcnt lgkmcnt(0)
	v_add_f32_e32 v46, v46, v47
	v_fmamk_f32 v46, v46, 0x3a800000, v171
	v_mul_f32_e32 v47, 0x4f800000, v46
	v_cmp_gt_f32_e32 vcc, s2, v46
	s_waitcnt vmcnt(0)
	v_pk_add_f32 v[40:41], v[40:41], 1.0 op_sel_hi:[1,0]
	v_pk_add_f32 v[38:39], v[38:39], 1.0 op_sel_hi:[1,0]
	v_pk_fma_f32 v[36:37], v[36:37], v[40:41], v[44:45]
	v_pk_fma_f32 v[34:35], v[34:35], v[38:39], v[42:43]
	v_bfe_u32 v40, v36, 16, 1
	v_bfe_u32 v38, v34, 16, 1
	v_bfe_u32 v39, v35, 16, 1
	v_bfe_u32 v41, v37, 16, 1
	v_add3_u32 v34, v34, v38, s3
	v_add3_u32 v36, v36, v40, s3
	v_add3_u32 v35, v35, v39, s3
	v_add3_u32 v37, v37, v41, s3
	v_lshrrev_b32_e32 v34, 16, v34
	v_lshrrev_b32_e32 v36, 16, v36
	v_and_or_b32 v34, v35, s21, v34
	v_and_or_b32 v35, v37, s21, v36
	global_store_dwordx2 v[104:105], v[34:35], off offset:1536
	global_load_dwordx4 v[34:37], v[144:145], off
	s_nop 0
	global_load_dwordx4 v[38:41], v[128:129], off
	v_cndmask_b32_e32 v42, v46, v47, vcc
	v_sqrt_f32_e32 v43, v42
	s_waitcnt vmcnt(0) lgkmcnt(0)
	v_pk_add_f32 v[36:37], v[36:37], 1.0 op_sel_hi:[1,0]
	v_add_u32_e32 v44, -1, v43
	v_add_u32_e32 v45, 1, v43
	v_fma_f32 v46, -v44, v43, v42
	v_fma_f32 v47, -v45, v43, v42
	v_cmp_ge_f32_e64 s[6:7], 0, v46
	v_pk_add_f32 v[34:35], v[34:35], 1.0 op_sel_hi:[1,0]
	s_nop 0
	v_cndmask_b32_e64 v43, v43, v44, s[6:7]
	v_cmp_lt_f32_e64 s[6:7], 0, v47
	s_nop 1
	v_cndmask_b32_e64 v43, v43, v45, s[6:7]
	v_mul_f32_e32 v44, 0x37800000, v43
	v_cndmask_b32_e32 v43, v43, v44, vcc
	v_cmp_class_f32_e32 vcc, v42, v172
	s_nop 1
	v_cndmask_b32_e32 v42, v43, v42, vcc
	v_div_scale_f32 v43, s[6:7], v42, v42, 1.0
	v_rcp_f32_e32 v45, v43
	v_div_scale_f32 v44, vcc, 1.0, v42, 1.0
	v_fma_f32 v46, -v43, v45, 1.0
	v_fmac_f32_e32 v45, v46, v45
	v_mul_f32_e32 v46, v44, v45
	v_fma_f32 v47, -v43, v46, v44
	v_fmac_f32_e32 v46, v47, v45
	v_fma_f32 v43, -v43, v46, v44
	v_div_fmas_f32 v43, v43, v45, v46
	v_div_fixup_f32 v42, v43, v42, 1.0
	v_pk_mul_f32 v[32:33], v[32:33], v[42:43] op_sel_hi:[1,0]
	v_pk_mul_f32 v[30:31], v[30:31], v[42:43] op_sel_hi:[1,0]
	v_pk_mul_f32 v[32:33], v[4:5], v[32:33]
	v_pk_mul_f32 v[30:31], v[2:3], v[30:31]
	v_pk_fma_f32 v[32:33], v[36:37], v[32:33], v[40:41]
	v_pk_fma_f32 v[30:31], v[34:35], v[30:31], v[38:39]
	v_bfe_u32 v36, v32, 16, 1
	v_bfe_u32 v34, v30, 16, 1
	v_bfe_u32 v35, v31, 16, 1
	v_bfe_u32 v37, v33, 16, 1
	v_add3_u32 v30, v30, v34, s3
	v_add3_u32 v32, v32, v36, s3
	v_add3_u32 v31, v31, v35, s3
	v_add3_u32 v33, v33, v37, s3
	v_lshrrev_b32_e32 v30, 16, v30
	v_lshrrev_b32_e32 v32, 16, v32
	v_and_or_b32 v30, v31, s21, v30
	v_and_or_b32 v31, v33, s21, v32
	global_store_dwordx2 v[104:105], v[30:31], off offset:2048
	global_load_dwordx4 v[30:33], v[124:125], off
	s_nop 0
	global_load_dwordx4 v[34:37], v[120:121], off
	v_pk_mul_f32 v[28:29], v[28:29], v[42:43] op_sel_hi:[1,0]
	v_pk_mul_f32 v[26:27], v[26:27], v[42:43] op_sel_hi:[1,0]
	v_pk_mul_f32 v[28:29], v[8:9], v[28:29]
	v_pk_mul_f32 v[26:27], v[6:7], v[26:27]
	v_lshl_add_u64 v[40:41], s[18:19], 0, v[98:99]
	v_lshl_add_u64 v[38:39], s[16:17], 0, v[98:99]
	v_pk_mul_f32 v[24:25], v[24:25], v[42:43] op_sel_hi:[1,0]
	v_pk_mul_f32 v[22:23], v[22:23], v[42:43] op_sel_hi:[1,0]
	v_pk_mul_f32 v[24:25], v[12:13], v[24:25]
	v_pk_mul_f32 v[22:23], v[10:11], v[22:23]
	v_pk_mul_f32 v[20:21], v[20:21], v[42:43] op_sel_hi:[1,0]
	v_pk_mul_f32 v[18:19], v[18:19], v[42:43] op_sel_hi:[1,0]
	v_pk_mul_f32 v[20:21], v[16:17], v[20:21]
	v_pk_mul_f32 v[18:19], v[14:15], v[18:19]
	s_waitcnt vmcnt(0) lgkmcnt(0)
	v_pk_add_f32 v[32:33], v[32:33], 1.0 op_sel_hi:[1,0]
	v_pk_add_f32 v[30:31], v[30:31], 1.0 op_sel_hi:[1,0]
	v_pk_fma_f32 v[28:29], v[32:33], v[28:29], v[36:37]
	v_pk_fma_f32 v[26:27], v[30:31], v[26:27], v[34:35]
	v_bfe_u32 v32, v28, 16, 1
	v_bfe_u32 v30, v26, 16, 1
	v_bfe_u32 v31, v27, 16, 1
	v_bfe_u32 v33, v29, 16, 1
	v_add3_u32 v26, v26, v30, s3
	v_add3_u32 v28, v28, v32, s3
	v_add3_u32 v27, v27, v31, s3
	v_add3_u32 v29, v29, v33, s3
	v_lshrrev_b32_e32 v26, 16, v26
	v_lshrrev_b32_e32 v28, 16, v28
	v_and_or_b32 v26, v27, s21, v26
	v_and_or_b32 v27, v29, s21, v28
	global_store_dwordx2 v[104:105], v[26:27], off offset:2560
	global_load_dwordx4 v[26:29], v[40:41], off
	s_nop 0
	global_load_dwordx4 v[30:33], v[38:39], off
	v_lshl_add_u64 v[36:37], s[18:19], 0, v[100:101]
	v_lshl_add_u64 v[34:35], s[16:17], 0, v[100:101]
	s_waitcnt vmcnt(0) lgkmcnt(0)
	v_pk_add_f32 v[28:29], v[28:29], 1.0 op_sel_hi:[1,0]
	v_pk_add_f32 v[26:27], v[26:27], 1.0 op_sel_hi:[1,0]
	v_pk_fma_f32 v[24:25], v[28:29], v[24:25], v[32:33]
	v_pk_fma_f32 v[22:23], v[26:27], v[22:23], v[30:31]
	v_bfe_u32 v28, v24, 16, 1
	v_bfe_u32 v26, v22, 16, 1
	v_bfe_u32 v27, v23, 16, 1
	v_bfe_u32 v29, v25, 16, 1
	v_add3_u32 v22, v22, v26, s3
	v_add3_u32 v24, v24, v28, s3
	v_add3_u32 v23, v23, v27, s3
	v_add3_u32 v25, v25, v29, s3
	v_lshrrev_b32_e32 v22, 16, v22
	v_lshrrev_b32_e32 v24, 16, v24
	v_and_or_b32 v22, v23, s21, v22
	v_and_or_b32 v23, v25, s21, v24
	global_store_dwordx2 v[104:105], v[22:23], off offset:3072
	global_load_dwordx4 v[22:25], v[36:37], off
	s_nop 0
	global_load_dwordx4 v[26:29], v[34:35], off
	s_waitcnt vmcnt(0) lgkmcnt(0)
	v_pk_add_f32 v[24:25], v[24:25], 1.0 op_sel_hi:[1,0]
	v_pk_add_f32 v[22:23], v[22:23], 1.0 op_sel_hi:[1,0]
	v_pk_fma_f32 v[20:21], v[20:21], v[24:25], v[28:29]
	v_pk_fma_f32 v[18:19], v[18:19], v[22:23], v[26:27]
	v_bfe_u32 v24, v20, 16, 1
	v_bfe_u32 v22, v18, 16, 1
	v_bfe_u32 v23, v19, 16, 1
	v_bfe_u32 v25, v21, 16, 1
	v_add3_u32 v18, v18, v22, s3
	v_add3_u32 v20, v20, v24, s3
	v_add3_u32 v19, v19, v23, s3
	v_add3_u32 v21, v21, v25, s3
	v_lshrrev_b32_e32 v18, 16, v18
	v_lshrrev_b32_e32 v20, 16, v20
	v_and_or_b32 v18, v19, s21, v18
	v_and_or_b32 v19, v21, s21, v20
	global_store_dwordx2 v[104:105], v[18:19], off offset:3584
	s_cbranch_scc1 .LBB0_5693

.LBB0_5756:
	v_mul_f32_e32 v130, 0xbfb8aa3b, v126
	v_exp_f32_e32 v130, v130
	v_mul_f32_e32 v138, 0xbfb8aa3b, v127
	v_exp_f32_e32 v138, v138
	s_lshl_b32 s5, s82, 7
	v_add_f32_e32 v133, 1.0, v130
	v_div_scale_f32 v134, s[8:9], v133, v133, v126
	v_rcp_f32_e32 v135, v134
	s_or_b32 s5, s35, s5
	v_or_b32_e32 v130, s5, v142
	v_add_u32_e32 v132, 0x4000, v1
	v_fma_f32 v136, -v134, v135, 1.0
	v_fmac_f32_e32 v135, v136, v135
	v_div_scale_f32 v136, vcc, v126, v133, v126
	v_mul_f32_e32 v137, v136, v135
	v_fma_f32 v139, -v134, v137, v136
	v_fmac_f32_e32 v137, v139, v135
	v_fma_f32 v134, -v134, v137, v136
	v_add_f32_e32 v136, 1.0, v138
	v_div_scale_f32 v138, s[8:9], v136, v136, v127
	v_rcp_f32_e32 v139, v138
	v_div_fmas_f32 v134, v134, v135, v137
	v_div_fixup_f32 v126, v134, v133, v126
	v_mul_f32_e32 v122, v126, v122
	v_fma_f32 v126, -v138, v139, 1.0
	v_fmac_f32_e32 v139, v126, v139
	v_div_scale_f32 v126, vcc, v127, v136, v127
	v_mul_f32_e32 v133, v126, v139
	v_fma_f32 v134, -v138, v133, v126
	v_fmac_f32_e32 v133, v134, v139
	v_mul_f32_e32 v134, 0xbfb8aa3b, v128
	v_exp_f32_e32 v134, v134
	v_fma_f32 v126, -v138, v133, v126
	v_div_fmas_f32 v126, v126, v139, v133
	v_div_fixup_f32 v126, v126, v136, v127
	v_add_f32_e32 v133, 1.0, v134
	v_div_scale_f32 v134, s[8:9], v133, v133, v128
	v_rcp_f32_e32 v135, v134
	v_mul_f32_e32 v123, v126, v123
	v_mul_f32_e32 v127, 0xbfb8aa3b, v129
	v_cvt_pk_bf16_f32 v122, v122, v123
	v_fma_f32 v123, -v134, v135, 1.0
	v_exp_f32_e32 v127, v127
	v_fmac_f32_e32 v135, v123, v135
	v_div_scale_f32 v123, vcc, v128, v133, v128
	v_mul_f32_e32 v126, v123, v135
	v_fma_f32 v136, -v134, v126, v123
	v_fmac_f32_e32 v126, v136, v135
	v_add_f32_e32 v127, 1.0, v127
	v_fma_f32 v123, -v134, v126, v123
	v_div_scale_f32 v134, s[8:9], v127, v127, v129
	v_rcp_f32_e32 v136, v134
	v_div_fmas_f32 v123, v123, v135, v126
	v_div_fixup_f32 v123, v123, v133, v128
	v_mul_f32_e32 v123, v123, v124
	v_fma_f32 v124, -v134, v136, 1.0
	v_fmac_f32_e32 v136, v124, v136
	v_div_scale_f32 v124, vcc, v129, v127, v129
	v_mul_f32_e32 v126, v124, v136
	v_fma_f32 v128, -v134, v126, v124
	v_fmac_f32_e32 v126, v128, v136
	v_mul_f32_e32 v128, 0xbfb8aa3b, v118
	v_exp_f32_e32 v128, v128
	v_fma_f32 v124, -v134, v126, v124
	v_div_fmas_f32 v124, v124, v136, v126
	v_div_fixup_f32 v124, v124, v127, v129
	v_add_f32_e32 v126, 1.0, v128
	v_div_scale_f32 v128, s[8:9], v126, v126, v118
	v_rcp_f32_e32 v133, v128
	v_mul_f32_e32 v124, v124, v125
	v_mul_f32_e32 v127, 0xbfb8aa3b, v119
	v_cvt_pk_bf16_f32 v123, v123, v124
	v_fma_f32 v124, -v128, v133, 1.0
	v_exp_f32_e32 v127, v127
	v_fmac_f32_e32 v133, v124, v133
	v_div_scale_f32 v124, vcc, v118, v126, v118
	v_mul_f32_e32 v125, v124, v133
	v_fma_f32 v129, -v128, v125, v124
	v_fmac_f32_e32 v125, v129, v133
	v_add_f32_e32 v127, 1.0, v127
	v_fma_f32 v124, -v128, v125, v124
	v_div_scale_f32 v128, s[8:9], v127, v127, v119
	v_rcp_f32_e32 v129, v128
	v_div_fmas_f32 v124, v124, v133, v125
	v_div_fixup_f32 v118, v124, v126, v118
	v_mul_f32_e32 v114, v118, v114
	v_fma_f32 v118, -v128, v129, 1.0
	v_fmac_f32_e32 v129, v118, v129
	v_div_scale_f32 v118, vcc, v119, v127, v119
	v_mul_f32_e32 v124, v118, v129
	v_fma_f32 v125, -v128, v124, v118
	v_fmac_f32_e32 v124, v125, v129
	v_mul_f32_e32 v125, 0xbfb8aa3b, v120
	v_exp_f32_e32 v125, v125
	v_fma_f32 v118, -v128, v124, v118
	v_div_fmas_f32 v118, v118, v129, v124
	v_div_fixup_f32 v118, v118, v127, v119
	v_add_f32_e32 v125, 1.0, v125
	v_div_scale_f32 v126, s[8:9], v125, v125, v120
	v_rcp_f32_e32 v128, v126
	v_mul_f32_e32 v115, v118, v115
	v_mul_f32_e32 v118, 0xbfb8aa3b, v121
	v_exp_f32_e32 v118, v118
	v_cvt_pk_bf16_f32 v124, v114, v115
	v_fma_f32 v114, -v126, v128, 1.0
	v_fmac_f32_e32 v128, v114, v128
	v_div_scale_f32 v114, vcc, v120, v125, v120
	v_mul_f32_e32 v115, v114, v128
	v_fma_f32 v119, -v126, v115, v114
	v_add_f32_e32 v118, 1.0, v118
	v_fmac_f32_e32 v115, v119, v128
	v_div_scale_f32 v119, s[8:9], v118, v118, v121
	v_fma_f32 v114, -v126, v115, v114
	v_rcp_f32_e32 v126, v119
	v_div_fmas_f32 v114, v114, v128, v115
	v_div_fixup_f32 v114, v114, v125, v120
	v_mul_f32_e32 v114, v114, v116
	v_fma_f32 v115, -v119, v126, 1.0
	v_fmac_f32_e32 v126, v115, v126
	v_div_scale_f32 v115, vcc, v121, v118, v121
	v_mul_f32_e32 v116, v115, v126
	v_fma_f32 v120, -v119, v116, v115
	v_fmac_f32_e32 v116, v120, v126
	v_fma_f32 v115, -v119, v116, v115
	v_div_fmas_f32 v115, v115, v126, v116
	v_div_fixup_f32 v115, v115, v118, v121
	v_mul_f32_e32 v115, v115, v117
	v_cvt_pk_bf16_f32 v125, v114, v115
	v_mul_f32_e32 v114, 0xbfb8aa3b, v110
	v_exp_f32_e32 v116, v114
	v_ashrrev_i32_e32 v131, 31, v130
	s_movk_i32 s5, 0x1600
	v_mov_b64_e32 v[114:115], s[18:19]
	v_add_f32_e32 v120, 1.0, v116
	v_div_scale_f32 v121, s[8:9], v120, v120, v110
	v_rcp_f32_e32 v126, v121
	v_mad_i64_i32 v[118:119], s[8:9], v132, s5, v[114:115]
	v_lshlrev_b64 v[116:117], 1, v[130:131]
	v_lshl_add_u64 v[118:119], v[118:119], 0, v[116:117]
	global_store_dwordx4 v[118:119], v[122:125], off
	v_fma_f32 v118, -v121, v126, 1.0
	v_fmac_f32_e32 v126, v118, v126
	v_mul_f32_e32 v122, 0xbfb8aa3b, v111
	v_div_scale_f32 v118, vcc, v110, v120, v110
	v_exp_f32_e32 v122, v122
	v_mul_f32_e32 v119, v118, v126
	v_fma_f32 v123, -v121, v119, v118
	v_fmac_f32_e32 v119, v123, v126
	v_fma_f32 v118, -v121, v119, v118
	v_add_f32_e32 v121, 1.0, v122
	v_div_scale_f32 v122, s[8:9], v121, v121, v111
	v_rcp_f32_e32 v123, v122
	v_div_fmas_f32 v118, v118, v126, v119
	v_div_fixup_f32 v110, v118, v120, v110
	v_mul_f32_e32 v106, v110, v106
	v_fma_f32 v110, -v122, v123, 1.0
	v_fmac_f32_e32 v123, v110, v123
	v_div_scale_f32 v110, vcc, v111, v121, v111
	v_mul_f32_e32 v118, v110, v123
	v_fma_f32 v119, -v122, v118, v110
	v_fmac_f32_e32 v118, v119, v123
	v_mul_f32_e32 v119, 0xbfb8aa3b, v112
	v_exp_f32_e32 v119, v119
	v_fma_f32 v110, -v122, v118, v110
	v_div_fmas_f32 v110, v110, v123, v118
	v_div_fixup_f32 v110, v110, v121, v111
	v_add_f32_e32 v118, 1.0, v119
	v_div_scale_f32 v119, s[8:9], v118, v118, v112
	v_rcp_f32_e32 v120, v119
	v_mul_f32_e32 v107, v110, v107
	v_mul_f32_e32 v111, 0xbfb8aa3b, v113
	v_cvt_pk_bf16_f32 v106, v106, v107
	v_fma_f32 v107, -v119, v120, 1.0
	v_exp_f32_e32 v111, v111
	v_fmac_f32_e32 v120, v107, v120
	v_div_scale_f32 v107, vcc, v112, v118, v112
	v_mul_f32_e32 v110, v107, v120
	v_fma_f32 v121, -v119, v110, v107
	v_fmac_f32_e32 v110, v121, v120
	v_add_f32_e32 v111, 1.0, v111
	v_fma_f32 v107, -v119, v110, v107
	v_div_scale_f32 v119, s[8:9], v111, v111, v113
	v_rcp_f32_e32 v121, v119
	v_div_fmas_f32 v107, v107, v120, v110
	v_div_fixup_f32 v107, v107, v118, v112
	v_mul_f32_e32 v107, v107, v108
	v_fma_f32 v108, -v119, v121, 1.0
	v_fmac_f32_e32 v121, v108, v121
	v_div_scale_f32 v108, vcc, v113, v111, v113
	v_mul_f32_e32 v110, v108, v121
	v_fma_f32 v112, -v119, v110, v108
	v_fmac_f32_e32 v110, v112, v121
	v_mul_f32_e32 v112, 0xbfb8aa3b, v102
	v_exp_f32_e32 v112, v112
	v_fma_f32 v108, -v119, v110, v108
	v_div_fmas_f32 v108, v108, v121, v110
	v_div_fixup_f32 v108, v108, v111, v113
	v_add_f32_e32 v110, 1.0, v112
	v_div_scale_f32 v112, s[8:9], v110, v110, v102
	v_rcp_f32_e32 v118, v112
	v_mul_f32_e32 v108, v108, v109
	v_mul_f32_e32 v111, 0xbfb8aa3b, v103
	v_cvt_pk_bf16_f32 v107, v107, v108
	v_fma_f32 v108, -v112, v118, 1.0
	v_exp_f32_e32 v111, v111
	v_fmac_f32_e32 v118, v108, v118
	v_div_scale_f32 v108, vcc, v102, v110, v102
	v_mul_f32_e32 v109, v108, v118
	v_fma_f32 v113, -v112, v109, v108
	v_fmac_f32_e32 v109, v113, v118
	v_add_f32_e32 v111, 1.0, v111
	v_fma_f32 v108, -v112, v109, v108
	v_div_scale_f32 v112, s[8:9], v111, v111, v103
	v_rcp_f32_e32 v113, v112
	v_div_fmas_f32 v108, v108, v118, v109
	v_div_fixup_f32 v102, v108, v110, v102
	v_mul_f32_e32 v98, v102, v98
	v_fma_f32 v102, -v112, v113, 1.0
	v_fmac_f32_e32 v113, v102, v113
	v_div_scale_f32 v102, vcc, v103, v111, v103
	v_mul_f32_e32 v108, v102, v113
	v_fma_f32 v109, -v112, v108, v102
	v_fmac_f32_e32 v108, v109, v113
	v_mul_f32_e32 v109, 0xbfb8aa3b, v104
	v_exp_f32_e32 v109, v109
	v_fma_f32 v102, -v112, v108, v102
	v_div_fmas_f32 v102, v102, v113, v108
	v_div_fixup_f32 v102, v102, v111, v103
	v_add_f32_e32 v109, 1.0, v109
	v_div_scale_f32 v110, s[8:9], v109, v109, v104
	v_rcp_f32_e32 v112, v110
	v_mul_f32_e32 v99, v102, v99
	v_mul_f32_e32 v102, 0xbfb8aa3b, v105
	v_exp_f32_e32 v102, v102
	v_cvt_pk_bf16_f32 v108, v98, v99
	v_fma_f32 v98, -v110, v112, 1.0
	v_fmac_f32_e32 v112, v98, v112
	v_div_scale_f32 v98, vcc, v104, v109, v104
	v_mul_f32_e32 v99, v98, v112
	v_fma_f32 v103, -v110, v99, v98
	v_add_f32_e32 v102, 1.0, v102
	v_fmac_f32_e32 v99, v103, v112
	v_div_scale_f32 v103, s[8:9], v102, v102, v105
	v_fma_f32 v98, -v110, v99, v98
	v_rcp_f32_e32 v110, v103
	v_div_fmas_f32 v98, v98, v112, v99
	v_div_fixup_f32 v98, v98, v109, v104
	v_mul_f32_e32 v98, v98, v100
	v_fma_f32 v99, -v103, v110, 1.0
	v_fmac_f32_e32 v110, v99, v110
	v_div_scale_f32 v99, vcc, v105, v102, v105
	v_mul_f32_e32 v100, v99, v110
	v_fma_f32 v104, -v103, v100, v99
	v_fmac_f32_e32 v100, v104, v110
	v_fma_f32 v99, -v103, v100, v99
	v_div_fmas_f32 v99, v99, v110, v100
	v_mul_f32_e32 v100, 0xbfb8aa3b, v94
	v_exp_f32_e32 v100, v100
	v_div_fixup_f32 v99, v99, v102, v105
	v_mul_f32_e32 v99, v99, v101
	v_cvt_pk_bf16_f32 v109, v98, v99
	v_add_f32_e32 v100, 1.0, v100
	v_div_scale_f32 v101, s[8:9], v100, v100, v94
	v_rcp_f32_e32 v102, v101
	v_add_u32_e32 v98, 0x4010, v1
	v_mad_i64_i32 v[98:99], s[8:9], v98, s5, v[114:115]
	v_lshl_add_u64 v[98:99], v[98:99], 0, v[116:117]
	global_store_dwordx4 v[98:99], v[106:109], off
	v_fma_f32 v98, -v101, v102, 1.0
	v_mul_f32_e32 v103, 0xbfb8aa3b, v95
	v_fmac_f32_e32 v102, v98, v102
	v_div_scale_f32 v98, vcc, v94, v100, v94
	v_exp_f32_e32 v103, v103
	v_mul_f32_e32 v99, v98, v102
	v_fma_f32 v104, -v101, v99, v98
	v_fmac_f32_e32 v99, v104, v102
	v_fma_f32 v98, -v101, v99, v98
	v_add_f32_e32 v101, 1.0, v103
	v_div_scale_f32 v103, s[8:9], v101, v101, v95
	v_rcp_f32_e32 v104, v103
	v_div_fmas_f32 v98, v98, v102, v99
	v_div_fixup_f32 v94, v98, v100, v94
	v_mul_f32_e32 v90, v94, v90
	v_fma_f32 v94, -v103, v104, 1.0
	v_fmac_f32_e32 v104, v94, v104
	v_div_scale_f32 v94, vcc, v95, v101, v95
	v_mul_f32_e32 v98, v94, v104
	v_fma_f32 v99, -v103, v98, v94
	v_fmac_f32_e32 v98, v99, v104
	v_mul_f32_e32 v99, 0xbfb8aa3b, v96
	v_exp_f32_e32 v99, v99
	v_fma_f32 v94, -v103, v98, v94
	v_div_fmas_f32 v94, v94, v104, v98
	v_div_fixup_f32 v94, v94, v101, v95
	v_add_f32_e32 v98, 1.0, v99
	v_div_scale_f32 v99, s[8:9], v98, v98, v96
	v_rcp_f32_e32 v100, v99
	v_mul_f32_e32 v91, v94, v91
	v_mul_f32_e32 v95, 0xbfb8aa3b, v97
	v_cvt_pk_bf16_f32 v90, v90, v91
	v_fma_f32 v91, -v99, v100, 1.0
	v_exp_f32_e32 v95, v95
	v_fmac_f32_e32 v100, v91, v100
	v_div_scale_f32 v91, vcc, v96, v98, v96
	v_mul_f32_e32 v94, v91, v100
	v_fma_f32 v101, -v99, v94, v91
	v_fmac_f32_e32 v94, v101, v100
	v_add_f32_e32 v95, 1.0, v95
	v_fma_f32 v91, -v99, v94, v91
	v_div_scale_f32 v99, s[8:9], v95, v95, v97
	v_rcp_f32_e32 v101, v99
	v_div_fmas_f32 v91, v91, v100, v94
	v_div_fixup_f32 v91, v91, v98, v96
	v_mul_f32_e32 v91, v91, v92
	v_fma_f32 v92, -v99, v101, 1.0
	v_fmac_f32_e32 v101, v92, v101
	v_div_scale_f32 v92, vcc, v97, v95, v97
	v_mul_f32_e32 v94, v92, v101
	v_fma_f32 v96, -v99, v94, v92
	v_fmac_f32_e32 v94, v96, v101
	v_mul_f32_e32 v96, 0xbfb8aa3b, v86
	v_exp_f32_e32 v96, v96
	v_fma_f32 v92, -v99, v94, v92
	v_div_fmas_f32 v92, v92, v101, v94
	v_div_fixup_f32 v92, v92, v95, v97
	v_add_f32_e32 v94, 1.0, v96
	v_div_scale_f32 v96, s[8:9], v94, v94, v86
	v_rcp_f32_e32 v98, v96
	v_mul_f32_e32 v92, v92, v93
	v_mul_f32_e32 v95, 0xbfb8aa3b, v87
	v_cvt_pk_bf16_f32 v91, v91, v92
	v_fma_f32 v92, -v96, v98, 1.0
	v_exp_f32_e32 v95, v95
	v_fmac_f32_e32 v98, v92, v98
	v_div_scale_f32 v92, vcc, v86, v94, v86
	v_mul_f32_e32 v93, v92, v98
	v_fma_f32 v97, -v96, v93, v92
	v_fmac_f32_e32 v93, v97, v98
	v_add_f32_e32 v95, 1.0, v95
	v_fma_f32 v92, -v96, v93, v92
	v_div_scale_f32 v96, s[8:9], v95, v95, v87
	v_rcp_f32_e32 v97, v96
	v_div_fmas_f32 v92, v92, v98, v93
	v_div_fixup_f32 v86, v92, v94, v86
	v_mul_f32_e32 v82, v86, v82
	v_fma_f32 v86, -v96, v97, 1.0
	v_fmac_f32_e32 v97, v86, v97
	v_div_scale_f32 v86, vcc, v87, v95, v87
	v_mul_f32_e32 v92, v86, v97
	v_fma_f32 v93, -v96, v92, v86
	v_fmac_f32_e32 v92, v93, v97
	v_mul_f32_e32 v93, 0xbfb8aa3b, v88
	v_exp_f32_e32 v93, v93
	v_fma_f32 v86, -v96, v92, v86
	v_div_fmas_f32 v86, v86, v97, v92
	v_div_fixup_f32 v86, v86, v95, v87
	v_add_f32_e32 v93, 1.0, v93
	v_div_scale_f32 v94, s[8:9], v93, v93, v88
	v_rcp_f32_e32 v96, v94
	v_mul_f32_e32 v83, v86, v83
	v_mul_f32_e32 v86, 0xbfb8aa3b, v89
	v_exp_f32_e32 v86, v86
	v_cvt_pk_bf16_f32 v92, v82, v83
	v_fma_f32 v82, -v94, v96, 1.0
	v_fmac_f32_e32 v96, v82, v96
	v_div_scale_f32 v82, vcc, v88, v93, v88
	v_mul_f32_e32 v83, v82, v96
	v_fma_f32 v87, -v94, v83, v82
	v_add_f32_e32 v86, 1.0, v86
	v_fmac_f32_e32 v83, v87, v96
	v_div_scale_f32 v87, s[8:9], v86, v86, v89
	v_fma_f32 v82, -v94, v83, v82
	v_rcp_f32_e32 v94, v87
	v_div_fmas_f32 v82, v82, v96, v83
	v_div_fixup_f32 v82, v82, v93, v88
	v_mul_f32_e32 v82, v82, v84
	v_fma_f32 v83, -v87, v94, 1.0
	v_fmac_f32_e32 v94, v83, v94
	v_div_scale_f32 v83, vcc, v89, v86, v89
	v_mul_f32_e32 v84, v83, v94
	v_fma_f32 v88, -v87, v84, v83
	v_fmac_f32_e32 v84, v88, v94
	v_fma_f32 v83, -v87, v84, v83
	v_div_fmas_f32 v83, v83, v94, v84
	v_mul_f32_e32 v84, 0xbfb8aa3b, v78
	v_exp_f32_e32 v84, v84
	v_div_fixup_f32 v83, v83, v86, v89
	v_mul_f32_e32 v83, v83, v85
	v_cvt_pk_bf16_f32 v93, v82, v83
	v_add_f32_e32 v84, 1.0, v84
	v_div_scale_f32 v85, s[8:9], v84, v84, v78
	v_rcp_f32_e32 v86, v85
	v_add_u32_e32 v82, 0x4020, v1
	v_mad_i64_i32 v[82:83], s[8:9], v82, s5, v[114:115]
	v_lshl_add_u64 v[82:83], v[82:83], 0, v[116:117]
	global_store_dwordx4 v[82:83], v[90:93], off
	v_fma_f32 v82, -v85, v86, 1.0
	v_mul_f32_e32 v87, 0xbfb8aa3b, v79
	v_fmac_f32_e32 v86, v82, v86
	v_div_scale_f32 v82, vcc, v78, v84, v78
	v_exp_f32_e32 v87, v87
	v_mul_f32_e32 v83, v82, v86
	v_fma_f32 v88, -v85, v83, v82
	v_fmac_f32_e32 v83, v88, v86
	v_fma_f32 v82, -v85, v83, v82
	v_add_f32_e32 v85, 1.0, v87
	v_div_scale_f32 v87, s[8:9], v85, v85, v79
	v_rcp_f32_e32 v88, v87
	v_div_fmas_f32 v82, v82, v86, v83
	v_div_fixup_f32 v78, v82, v84, v78
	v_mul_f32_e32 v74, v78, v74
	v_fma_f32 v78, -v87, v88, 1.0
	v_fmac_f32_e32 v88, v78, v88
	v_div_scale_f32 v78, vcc, v79, v85, v79
	v_mul_f32_e32 v82, v78, v88
	v_fma_f32 v83, -v87, v82, v78
	v_fmac_f32_e32 v82, v83, v88
	v_mul_f32_e32 v83, 0xbfb8aa3b, v80
	v_exp_f32_e32 v83, v83
	v_fma_f32 v78, -v87, v82, v78
	v_div_fmas_f32 v78, v78, v88, v82
	v_div_fixup_f32 v78, v78, v85, v79
	v_add_f32_e32 v82, 1.0, v83
	v_div_scale_f32 v83, s[8:9], v82, v82, v80
	v_rcp_f32_e32 v84, v83
	v_mul_f32_e32 v75, v78, v75
	v_mul_f32_e32 v79, 0xbfb8aa3b, v81
	v_cvt_pk_bf16_f32 v74, v74, v75
	v_fma_f32 v75, -v83, v84, 1.0
	v_exp_f32_e32 v79, v79
	v_fmac_f32_e32 v84, v75, v84
	v_div_scale_f32 v75, vcc, v80, v82, v80
	v_mul_f32_e32 v78, v75, v84
	v_fma_f32 v85, -v83, v78, v75
	v_fmac_f32_e32 v78, v85, v84
	v_add_f32_e32 v79, 1.0, v79
	v_fma_f32 v75, -v83, v78, v75
	v_div_scale_f32 v83, s[8:9], v79, v79, v81
	v_rcp_f32_e32 v85, v83
	v_div_fmas_f32 v75, v75, v84, v78
	v_div_fixup_f32 v75, v75, v82, v80
	v_mul_f32_e32 v75, v75, v76
	v_fma_f32 v76, -v83, v85, 1.0
	v_fmac_f32_e32 v85, v76, v85
	v_div_scale_f32 v76, vcc, v81, v79, v81
	v_mul_f32_e32 v78, v76, v85
	v_fma_f32 v80, -v83, v78, v76
	v_fmac_f32_e32 v78, v80, v85
	v_mul_f32_e32 v80, 0xbfb8aa3b, v70
	v_exp_f32_e32 v80, v80
	v_fma_f32 v76, -v83, v78, v76
	v_div_fmas_f32 v76, v76, v85, v78
	v_div_fixup_f32 v76, v76, v79, v81
	v_add_f32_e32 v78, 1.0, v80
	v_div_scale_f32 v80, s[8:9], v78, v78, v70
	v_rcp_f32_e32 v82, v80
	v_mul_f32_e32 v76, v76, v77
	v_mul_f32_e32 v79, 0xbfb8aa3b, v71
	v_cvt_pk_bf16_f32 v75, v75, v76
	v_fma_f32 v76, -v80, v82, 1.0
	v_exp_f32_e32 v79, v79
	v_fmac_f32_e32 v82, v76, v82
	v_div_scale_f32 v76, vcc, v70, v78, v70
	v_mul_f32_e32 v77, v76, v82
	v_fma_f32 v81, -v80, v77, v76
	v_fmac_f32_e32 v77, v81, v82
	v_add_f32_e32 v79, 1.0, v79
	v_fma_f32 v76, -v80, v77, v76
	v_div_scale_f32 v80, s[8:9], v79, v79, v71
	v_rcp_f32_e32 v81, v80
	v_div_fmas_f32 v76, v76, v82, v77
	v_div_fixup_f32 v70, v76, v78, v70
	v_mul_f32_e32 v66, v70, v66
	v_fma_f32 v70, -v80, v81, 1.0
	v_fmac_f32_e32 v81, v70, v81
	v_div_scale_f32 v70, vcc, v71, v79, v71
	v_mul_f32_e32 v76, v70, v81
	v_fma_f32 v77, -v80, v76, v70
	v_fmac_f32_e32 v76, v77, v81
	v_mul_f32_e32 v77, 0xbfb8aa3b, v72
	v_exp_f32_e32 v77, v77
	v_fma_f32 v70, -v80, v76, v70
	v_div_fmas_f32 v70, v70, v81, v76
	v_div_fixup_f32 v70, v70, v79, v71
	v_add_f32_e32 v77, 1.0, v77
	v_div_scale_f32 v78, s[8:9], v77, v77, v72
	v_rcp_f32_e32 v80, v78
	v_mul_f32_e32 v67, v70, v67
	v_mul_f32_e32 v70, 0xbfb8aa3b, v73
	v_exp_f32_e32 v70, v70
	v_cvt_pk_bf16_f32 v76, v66, v67
	v_fma_f32 v66, -v78, v80, 1.0
	v_fmac_f32_e32 v80, v66, v80
	v_div_scale_f32 v66, vcc, v72, v77, v72
	v_mul_f32_e32 v67, v66, v80
	v_fma_f32 v71, -v78, v67, v66
	v_add_f32_e32 v70, 1.0, v70
	v_fmac_f32_e32 v67, v71, v80
	v_div_scale_f32 v71, s[8:9], v70, v70, v73
	v_fma_f32 v66, -v78, v67, v66
	v_rcp_f32_e32 v78, v71
	v_div_fmas_f32 v66, v66, v80, v67
	v_div_fixup_f32 v66, v66, v77, v72
	v_mul_f32_e32 v66, v66, v68
	v_fma_f32 v67, -v71, v78, 1.0
	v_fmac_f32_e32 v78, v67, v78
	v_div_scale_f32 v67, vcc, v73, v70, v73
	v_mul_f32_e32 v68, v67, v78
	v_fma_f32 v72, -v71, v68, v67
	v_fmac_f32_e32 v68, v72, v78
	v_fma_f32 v67, -v71, v68, v67
	v_div_fmas_f32 v67, v67, v78, v68
	v_div_fixup_f32 v67, v67, v70, v73
	v_mul_f32_e32 v67, v67, v69
	v_cvt_pk_bf16_f32 v77, v66, v67
	v_mul_f32_e32 v66, 0xbfb8aa3b, v62
	v_exp_f32_e32 v68, v66
	v_add_u32_e32 v66, 0x4030, v1
	v_mad_i64_i32 v[66:67], s[8:9], v66, s5, v[114:115]
	v_add_f32_e32 v68, 1.0, v68
	v_div_scale_f32 v69, s[8:9], v68, v68, v62
	v_rcp_f32_e32 v70, v69
	v_lshl_add_u64 v[66:67], v[66:67], 0, v[116:117]
	global_store_dwordx4 v[66:67], v[74:77], off
	v_mul_f32_e32 v72, 0xbfb8aa3b, v63
	v_fma_f32 v67, -v69, v70, 1.0
	v_fmac_f32_e32 v70, v67, v70
	v_div_scale_f32 v67, vcc, v62, v68, v62
	v_exp_f32_e32 v72, v72
	v_mul_f32_e32 v71, v67, v70
	v_fma_f32 v73, -v69, v71, v67
	v_fmac_f32_e32 v71, v73, v70
	v_fma_f32 v67, -v69, v71, v67
	v_add_f32_e32 v69, 1.0, v72
	v_div_scale_f32 v72, s[8:9], v69, v69, v63
	v_rcp_f32_e32 v73, v72
	v_div_fmas_f32 v67, v67, v70, v71
	v_div_fixup_f32 v62, v67, v68, v62
	v_mul_f32_e32 v58, v62, v58
	v_fma_f32 v62, -v72, v73, 1.0
	v_fmac_f32_e32 v73, v62, v73
	v_div_scale_f32 v62, vcc, v63, v69, v63
	v_mul_f32_e32 v67, v62, v73
	v_fma_f32 v68, -v72, v67, v62
	v_fmac_f32_e32 v67, v68, v73
	v_mul_f32_e32 v68, 0xbfb8aa3b, v64
	v_exp_f32_e32 v68, v68
	v_fma_f32 v62, -v72, v67, v62
	v_div_fmas_f32 v62, v62, v73, v67
	v_div_fixup_f32 v62, v62, v69, v63
	v_add_f32_e32 v67, 1.0, v68
	v_div_scale_f32 v68, s[8:9], v67, v67, v64
	v_rcp_f32_e32 v70, v68
	v_mul_f32_e32 v59, v62, v59
	v_mul_f32_e32 v63, 0xbfb8aa3b, v65
	v_cvt_pk_bf16_f32 v58, v58, v59
	v_fma_f32 v59, -v68, v70, 1.0
	v_exp_f32_e32 v63, v63
	v_fmac_f32_e32 v70, v59, v70
	v_div_scale_f32 v59, vcc, v64, v67, v64
	v_mul_f32_e32 v62, v59, v70
	v_fma_f32 v69, -v68, v62, v59
	v_fmac_f32_e32 v62, v69, v70
	v_add_f32_e32 v63, 1.0, v63
	v_fma_f32 v59, -v68, v62, v59
	v_div_scale_f32 v68, s[8:9], v63, v63, v65
	v_rcp_f32_e32 v69, v68
	v_div_fmas_f32 v59, v59, v70, v62
	v_div_fixup_f32 v59, v59, v67, v64
	v_mul_f32_e32 v59, v59, v60
	v_fma_f32 v60, -v68, v69, 1.0
	v_fmac_f32_e32 v69, v60, v69
	v_div_scale_f32 v60, vcc, v65, v63, v65
	v_mul_f32_e32 v62, v60, v69
	v_fma_f32 v64, -v68, v62, v60
	v_fmac_f32_e32 v62, v64, v69
	v_mul_f32_e32 v64, 0xbfb8aa3b, v54
	v_exp_f32_e32 v64, v64
	v_fma_f32 v60, -v68, v62, v60
	v_div_fmas_f32 v60, v60, v69, v62
	v_div_fixup_f32 v60, v60, v63, v65
	v_add_f32_e32 v62, 1.0, v64
	v_div_scale_f32 v64, s[8:9], v62, v62, v54
	v_rcp_f32_e32 v67, v64
	v_mul_f32_e32 v60, v60, v61
	v_mul_f32_e32 v63, 0xbfb8aa3b, v55
	v_cvt_pk_bf16_f32 v59, v59, v60
	v_fma_f32 v60, -v64, v67, 1.0
	v_exp_f32_e32 v63, v63
	v_fmac_f32_e32 v67, v60, v67
	v_div_scale_f32 v60, vcc, v54, v62, v54
	v_mul_f32_e32 v61, v60, v67
	v_fma_f32 v65, -v64, v61, v60
	v_fmac_f32_e32 v61, v65, v67
	v_add_f32_e32 v63, 1.0, v63
	v_fma_f32 v60, -v64, v61, v60
	v_div_scale_f32 v64, s[8:9], v63, v63, v55
	v_rcp_f32_e32 v65, v64
	v_div_fmas_f32 v60, v60, v67, v61
	v_div_fixup_f32 v54, v60, v62, v54
	v_mul_f32_e32 v50, v54, v50
	v_fma_f32 v54, -v64, v65, 1.0
	v_fmac_f32_e32 v65, v54, v65
	v_div_scale_f32 v54, vcc, v55, v63, v55
	v_mul_f32_e32 v60, v54, v65
	v_fma_f32 v61, -v64, v60, v54
	v_fmac_f32_e32 v60, v61, v65
	v_mul_f32_e32 v61, 0xbfb8aa3b, v56
	v_exp_f32_e32 v61, v61
	v_fma_f32 v54, -v64, v60, v54
	v_div_fmas_f32 v54, v54, v65, v60
	v_div_fixup_f32 v54, v54, v63, v55
	v_add_f32_e32 v61, 1.0, v61
	v_div_scale_f32 v62, s[8:9], v61, v61, v56
	v_rcp_f32_e32 v64, v62
	v_mul_f32_e32 v51, v54, v51
	v_mul_f32_e32 v54, 0xbfb8aa3b, v57
	v_exp_f32_e32 v54, v54
	v_cvt_pk_bf16_f32 v60, v50, v51
	v_fma_f32 v50, -v62, v64, 1.0
	v_fmac_f32_e32 v64, v50, v64
	v_div_scale_f32 v50, vcc, v56, v61, v56
	v_mul_f32_e32 v51, v50, v64
	v_fma_f32 v55, -v62, v51, v50
	v_add_f32_e32 v54, 1.0, v54
	v_fmac_f32_e32 v51, v55, v64
	v_div_scale_f32 v55, s[8:9], v54, v54, v57
	v_fma_f32 v50, -v62, v51, v50
	v_rcp_f32_e32 v62, v55
	v_div_fmas_f32 v50, v50, v64, v51
	v_div_fixup_f32 v50, v50, v61, v56
	v_mul_f32_e32 v50, v50, v52
	v_fma_f32 v51, -v55, v62, 1.0
	v_fmac_f32_e32 v62, v51, v62
	v_div_scale_f32 v51, vcc, v57, v54, v57
	v_mul_f32_e32 v52, v51, v62
	v_fma_f32 v56, -v55, v52, v51
	v_fmac_f32_e32 v52, v56, v62
	v_fma_f32 v51, -v55, v52, v51
	v_div_fmas_f32 v51, v51, v62, v52
	v_mul_f32_e32 v52, 0xbfb8aa3b, v46
	v_exp_f32_e32 v52, v52
	v_div_fixup_f32 v51, v51, v54, v57
	v_mul_f32_e32 v51, v51, v53
	v_add_u32_e32 v66, 0x4080, v1
	v_add_f32_e32 v52, 1.0, v52
	v_div_scale_f32 v53, s[8:9], v52, v52, v46
	v_rcp_f32_e32 v54, v53
	v_cvt_pk_bf16_f32 v61, v50, v51
	v_mad_i64_i32 v[50:51], s[8:9], v66, s5, v[114:115]
	v_lshl_add_u64 v[50:51], v[50:51], 0, v[116:117]
	global_store_dwordx4 v[50:51], v[58:61], off
	v_fma_f32 v50, -v53, v54, 1.0
	v_mul_f32_e32 v55, 0xbfb8aa3b, v47
	v_fmac_f32_e32 v54, v50, v54
	v_div_scale_f32 v50, vcc, v46, v52, v46
	v_exp_f32_e32 v55, v55
	v_mul_f32_e32 v51, v50, v54
	v_fma_f32 v56, -v53, v51, v50
	v_fmac_f32_e32 v51, v56, v54
	v_fma_f32 v50, -v53, v51, v50
	v_add_f32_e32 v53, 1.0, v55
	v_div_scale_f32 v55, s[8:9], v53, v53, v47
	v_rcp_f32_e32 v56, v55
	v_div_fmas_f32 v50, v50, v54, v51
	v_div_fixup_f32 v46, v50, v52, v46
	v_mul_f32_e32 v42, v46, v42
	v_fma_f32 v46, -v55, v56, 1.0
	v_fmac_f32_e32 v56, v46, v56
	v_div_scale_f32 v46, vcc, v47, v53, v47
	v_mul_f32_e32 v50, v46, v56
	v_fma_f32 v51, -v55, v50, v46
	v_fmac_f32_e32 v50, v51, v56
	v_mul_f32_e32 v51, 0xbfb8aa3b, v48
	v_exp_f32_e32 v51, v51
	v_fma_f32 v46, -v55, v50, v46
	v_div_fmas_f32 v46, v46, v56, v50
	v_div_fixup_f32 v46, v46, v53, v47
	v_add_f32_e32 v50, 1.0, v51
	v_div_scale_f32 v51, s[8:9], v50, v50, v48
	v_rcp_f32_e32 v52, v51
	v_mul_f32_e32 v43, v46, v43
	v_mul_f32_e32 v47, 0xbfb8aa3b, v49
	v_cvt_pk_bf16_f32 v42, v42, v43
	v_fma_f32 v43, -v51, v52, 1.0
	v_exp_f32_e32 v47, v47
	v_fmac_f32_e32 v52, v43, v52
	v_div_scale_f32 v43, vcc, v48, v50, v48
	v_mul_f32_e32 v46, v43, v52
	v_fma_f32 v53, -v51, v46, v43
	v_fmac_f32_e32 v46, v53, v52
	v_add_f32_e32 v47, 1.0, v47
	v_fma_f32 v43, -v51, v46, v43
	v_div_scale_f32 v51, s[8:9], v47, v47, v49
	v_rcp_f32_e32 v53, v51
	v_div_fmas_f32 v43, v43, v52, v46
	v_div_fixup_f32 v43, v43, v50, v48
	v_mul_f32_e32 v43, v43, v44
	v_fma_f32 v44, -v51, v53, 1.0
	v_fmac_f32_e32 v53, v44, v53
	v_div_scale_f32 v44, vcc, v49, v47, v49
	v_mul_f32_e32 v46, v44, v53
	v_fma_f32 v48, -v51, v46, v44
	v_fmac_f32_e32 v46, v48, v53
	v_mul_f32_e32 v48, 0xbfb8aa3b, v38
	v_exp_f32_e32 v48, v48
	v_fma_f32 v44, -v51, v46, v44
	v_div_fmas_f32 v44, v44, v53, v46
	v_div_fixup_f32 v44, v44, v47, v49
	v_add_f32_e32 v46, 1.0, v48
	v_div_scale_f32 v48, s[8:9], v46, v46, v38
	v_rcp_f32_e32 v50, v48
	v_mul_f32_e32 v44, v44, v45
	v_mul_f32_e32 v47, 0xbfb8aa3b, v39
	v_cvt_pk_bf16_f32 v43, v43, v44
	v_fma_f32 v44, -v48, v50, 1.0
	v_exp_f32_e32 v47, v47
	v_fmac_f32_e32 v50, v44, v50
	v_div_scale_f32 v44, vcc, v38, v46, v38
	v_mul_f32_e32 v45, v44, v50
	v_fma_f32 v49, -v48, v45, v44
	v_fmac_f32_e32 v45, v49, v50
	v_add_f32_e32 v47, 1.0, v47
	v_fma_f32 v44, -v48, v45, v44
	v_div_scale_f32 v48, s[8:9], v47, v47, v39
	v_rcp_f32_e32 v49, v48
	v_div_fmas_f32 v44, v44, v50, v45
	v_div_fixup_f32 v38, v44, v46, v38
	v_mul_f32_e32 v34, v38, v34
	v_fma_f32 v38, -v48, v49, 1.0
	v_fmac_f32_e32 v49, v38, v49
	v_div_scale_f32 v38, vcc, v39, v47, v39
	v_mul_f32_e32 v44, v38, v49
	v_fma_f32 v45, -v48, v44, v38
	v_fmac_f32_e32 v44, v45, v49
	v_mul_f32_e32 v45, 0xbfb8aa3b, v40
	v_exp_f32_e32 v45, v45
	v_fma_f32 v38, -v48, v44, v38
	v_div_fmas_f32 v38, v38, v49, v44
	v_div_fixup_f32 v38, v38, v47, v39
	v_add_f32_e32 v45, 1.0, v45
	v_div_scale_f32 v46, s[8:9], v45, v45, v40
	v_rcp_f32_e32 v48, v46
	v_mul_f32_e32 v35, v38, v35
	v_mul_f32_e32 v38, 0xbfb8aa3b, v41
	v_exp_f32_e32 v38, v38
	v_cvt_pk_bf16_f32 v44, v34, v35
	v_fma_f32 v34, -v46, v48, 1.0
	v_fmac_f32_e32 v48, v34, v48
	v_div_scale_f32 v34, vcc, v40, v45, v40
	v_mul_f32_e32 v35, v34, v48
	v_fma_f32 v39, -v46, v35, v34
	v_add_f32_e32 v38, 1.0, v38
	v_fmac_f32_e32 v35, v39, v48
	v_div_scale_f32 v39, s[8:9], v38, v38, v41
	v_fma_f32 v34, -v46, v35, v34
	v_rcp_f32_e32 v46, v39
	v_div_fmas_f32 v34, v34, v48, v35
	v_div_fixup_f32 v34, v34, v45, v40
	v_mul_f32_e32 v34, v34, v36
	v_fma_f32 v35, -v39, v46, 1.0
	v_fmac_f32_e32 v46, v35, v46
	v_div_scale_f32 v35, vcc, v41, v38, v41
	v_mul_f32_e32 v36, v35, v46
	v_fma_f32 v40, -v39, v36, v35
	v_fmac_f32_e32 v36, v40, v46
	v_fma_f32 v35, -v39, v36, v35
	v_div_fmas_f32 v35, v35, v46, v36
	v_mul_f32_e32 v36, 0xbfb8aa3b, v30
	v_exp_f32_e32 v36, v36
	v_div_fixup_f32 v35, v35, v38, v41
	v_mul_f32_e32 v35, v35, v37
	v_cvt_pk_bf16_f32 v45, v34, v35
	v_add_f32_e32 v36, 1.0, v36
	v_div_scale_f32 v37, s[8:9], v36, v36, v30
	v_rcp_f32_e32 v38, v37
	v_add_u32_e32 v34, 0x4090, v1
	v_mad_i64_i32 v[34:35], s[8:9], v34, s5, v[114:115]
	v_lshl_add_u64 v[34:35], v[34:35], 0, v[116:117]
	global_store_dwordx4 v[34:35], v[42:45], off
	v_fma_f32 v34, -v37, v38, 1.0
	v_mul_f32_e32 v39, 0xbfb8aa3b, v31
	v_fmac_f32_e32 v38, v34, v38
	v_div_scale_f32 v34, vcc, v30, v36, v30
	v_exp_f32_e32 v39, v39
	v_mul_f32_e32 v35, v34, v38
	v_fma_f32 v40, -v37, v35, v34
	v_fmac_f32_e32 v35, v40, v38
	v_fma_f32 v34, -v37, v35, v34
	v_add_f32_e32 v37, 1.0, v39
	v_div_scale_f32 v39, s[8:9], v37, v37, v31
	v_rcp_f32_e32 v40, v39
	v_div_fmas_f32 v34, v34, v38, v35
	v_div_fixup_f32 v30, v34, v36, v30
	v_mul_f32_e32 v26, v30, v26
	v_fma_f32 v30, -v39, v40, 1.0
	v_fmac_f32_e32 v40, v30, v40
	v_div_scale_f32 v30, vcc, v31, v37, v31
	v_mul_f32_e32 v34, v30, v40
	v_fma_f32 v35, -v39, v34, v30
	v_fmac_f32_e32 v34, v35, v40
	v_mul_f32_e32 v35, 0xbfb8aa3b, v32
	v_exp_f32_e32 v35, v35
	v_fma_f32 v30, -v39, v34, v30
	v_div_fmas_f32 v30, v30, v40, v34
	v_div_fixup_f32 v30, v30, v37, v31
	v_add_f32_e32 v34, 1.0, v35
	v_div_scale_f32 v35, s[8:9], v34, v34, v32
	v_rcp_f32_e32 v36, v35
	v_mul_f32_e32 v27, v30, v27
	v_mul_f32_e32 v31, 0xbfb8aa3b, v33
	v_cvt_pk_bf16_f32 v26, v26, v27
	v_fma_f32 v27, -v35, v36, 1.0
	v_exp_f32_e32 v31, v31
	v_fmac_f32_e32 v36, v27, v36
	v_div_scale_f32 v27, vcc, v32, v34, v32
	v_mul_f32_e32 v30, v27, v36
	v_fma_f32 v37, -v35, v30, v27
	v_fmac_f32_e32 v30, v37, v36
	v_add_f32_e32 v31, 1.0, v31
	v_fma_f32 v27, -v35, v30, v27
	v_div_scale_f32 v35, s[8:9], v31, v31, v33
	v_rcp_f32_e32 v37, v35
	v_div_fmas_f32 v27, v27, v36, v30
	v_div_fixup_f32 v27, v27, v34, v32
	v_mul_f32_e32 v27, v27, v28
	v_fma_f32 v28, -v35, v37, 1.0
	v_fmac_f32_e32 v37, v28, v37
	v_div_scale_f32 v28, vcc, v33, v31, v33
	v_mul_f32_e32 v30, v28, v37
	v_fma_f32 v32, -v35, v30, v28
	v_fmac_f32_e32 v30, v32, v37
	v_mul_f32_e32 v32, 0xbfb8aa3b, v22
	v_exp_f32_e32 v32, v32
	v_fma_f32 v28, -v35, v30, v28
	v_div_fmas_f32 v28, v28, v37, v30
	v_div_fixup_f32 v28, v28, v31, v33
	v_add_f32_e32 v30, 1.0, v32
	v_div_scale_f32 v32, s[8:9], v30, v30, v22
	v_rcp_f32_e32 v34, v32
	v_mul_f32_e32 v28, v28, v29
	v_mul_f32_e32 v31, 0xbfb8aa3b, v23
	v_cvt_pk_bf16_f32 v27, v27, v28
	v_fma_f32 v28, -v32, v34, 1.0
	v_exp_f32_e32 v31, v31
	v_fmac_f32_e32 v34, v28, v34
	v_div_scale_f32 v28, vcc, v22, v30, v22
	v_mul_f32_e32 v29, v28, v34
	v_fma_f32 v33, -v32, v29, v28
	v_fmac_f32_e32 v29, v33, v34
	v_add_f32_e32 v31, 1.0, v31
	v_fma_f32 v28, -v32, v29, v28
	v_div_scale_f32 v32, s[8:9], v31, v31, v23
	v_rcp_f32_e32 v33, v32
	v_div_fmas_f32 v28, v28, v34, v29
	v_div_fixup_f32 v22, v28, v30, v22
	v_mul_f32_e32 v18, v22, v18
	v_fma_f32 v22, -v32, v33, 1.0
	v_fmac_f32_e32 v33, v22, v33
	v_div_scale_f32 v22, vcc, v23, v31, v23
	v_mul_f32_e32 v28, v22, v33
	v_fma_f32 v29, -v32, v28, v22
	v_fmac_f32_e32 v28, v29, v33
	v_mul_f32_e32 v29, 0xbfb8aa3b, v24
	v_exp_f32_e32 v29, v29
	v_fma_f32 v22, -v32, v28, v22
	v_div_fmas_f32 v22, v22, v33, v28
	v_div_fixup_f32 v22, v22, v31, v23
	v_add_f32_e32 v29, 1.0, v29
	v_div_scale_f32 v30, s[8:9], v29, v29, v24
	v_rcp_f32_e32 v32, v30
	v_mul_f32_e32 v19, v22, v19
	v_mul_f32_e32 v22, 0xbfb8aa3b, v25
	v_exp_f32_e32 v22, v22
	v_cvt_pk_bf16_f32 v28, v18, v19
	v_fma_f32 v18, -v30, v32, 1.0
	v_fmac_f32_e32 v32, v18, v32
	v_div_scale_f32 v18, vcc, v24, v29, v24
	v_mul_f32_e32 v19, v18, v32
	v_fma_f32 v23, -v30, v19, v18
	v_add_f32_e32 v22, 1.0, v22
	v_fmac_f32_e32 v19, v23, v32
	v_div_scale_f32 v23, s[8:9], v22, v22, v25
	v_fma_f32 v18, -v30, v19, v18
	v_rcp_f32_e32 v30, v23
	v_div_fmas_f32 v18, v18, v32, v19
	v_div_fixup_f32 v18, v18, v29, v24
	v_mul_f32_e32 v18, v18, v20
	v_fma_f32 v19, -v23, v30, 1.0
	v_fmac_f32_e32 v30, v19, v30
	v_div_scale_f32 v19, vcc, v25, v22, v25
	v_mul_f32_e32 v20, v19, v30
	v_fma_f32 v24, -v23, v20, v19
	v_fmac_f32_e32 v20, v24, v30
	v_fma_f32 v19, -v23, v20, v19
	v_div_fmas_f32 v19, v19, v30, v20
	v_mul_f32_e32 v20, 0xbfb8aa3b, v14
	v_exp_f32_e32 v20, v20
	v_div_fixup_f32 v19, v19, v22, v25
	v_mul_f32_e32 v19, v19, v21
	v_cvt_pk_bf16_f32 v29, v18, v19
	v_add_f32_e32 v20, 1.0, v20
	v_div_scale_f32 v21, s[8:9], v20, v20, v14
	v_rcp_f32_e32 v22, v21
	v_add_u32_e32 v18, 0x40a0, v1
	v_mad_i64_i32 v[18:19], s[8:9], v18, s5, v[114:115]
	v_lshl_add_u64 v[18:19], v[18:19], 0, v[116:117]
	global_store_dwordx4 v[18:19], v[26:29], off
	v_fma_f32 v18, -v21, v22, 1.0
	v_mul_f32_e32 v23, 0xbfb8aa3b, v15
	v_fmac_f32_e32 v22, v18, v22
	v_div_scale_f32 v18, vcc, v14, v20, v14
	v_exp_f32_e32 v23, v23
	v_mul_f32_e32 v19, v18, v22
	v_fma_f32 v24, -v21, v19, v18
	v_fmac_f32_e32 v19, v24, v22
	v_fma_f32 v18, -v21, v19, v18
	v_add_f32_e32 v21, 1.0, v23
	v_div_scale_f32 v23, s[8:9], v21, v21, v15
	v_rcp_f32_e32 v24, v23
	v_div_fmas_f32 v18, v18, v22, v19
	v_div_fixup_f32 v14, v18, v20, v14
	v_mul_f32_e32 v10, v14, v10
	v_fma_f32 v14, -v23, v24, 1.0
	v_fmac_f32_e32 v24, v14, v24
	v_div_scale_f32 v14, vcc, v15, v21, v15
	v_mul_f32_e32 v18, v14, v24
	v_fma_f32 v19, -v23, v18, v14
	v_fmac_f32_e32 v18, v19, v24
	v_mul_f32_e32 v19, 0xbfb8aa3b, v16
	v_exp_f32_e32 v19, v19
	v_fma_f32 v14, -v23, v18, v14
	v_div_fmas_f32 v14, v14, v24, v18
	v_div_fixup_f32 v14, v14, v21, v15
	v_add_f32_e32 v18, 1.0, v19
	v_div_scale_f32 v19, s[8:9], v18, v18, v16
	v_rcp_f32_e32 v20, v19
	v_mul_f32_e32 v11, v14, v11
	v_mul_f32_e32 v15, 0xbfb8aa3b, v17
	v_cvt_pk_bf16_f32 v10, v10, v11
	v_fma_f32 v11, -v19, v20, 1.0
	v_exp_f32_e32 v15, v15
	v_fmac_f32_e32 v20, v11, v20
	v_div_scale_f32 v11, vcc, v16, v18, v16
	v_mul_f32_e32 v14, v11, v20
	v_fma_f32 v21, -v19, v14, v11
	v_fmac_f32_e32 v14, v21, v20
	v_add_f32_e32 v15, 1.0, v15
	v_fma_f32 v11, -v19, v14, v11
	v_div_scale_f32 v19, s[8:9], v15, v15, v17
	v_rcp_f32_e32 v21, v19
	v_div_fmas_f32 v11, v11, v20, v14
	v_div_fixup_f32 v11, v11, v18, v16
	v_mul_f32_e32 v11, v11, v12
	v_fma_f32 v12, -v19, v21, 1.0
	v_fmac_f32_e32 v21, v12, v21
	v_div_scale_f32 v12, vcc, v17, v15, v17
	v_mul_f32_e32 v14, v12, v21
	v_fma_f32 v16, -v19, v14, v12
	v_fmac_f32_e32 v14, v16, v21
	v_mul_f32_e32 v16, 0xbfb8aa3b, v6
	v_exp_f32_e32 v16, v16
	v_fma_f32 v12, -v19, v14, v12
	v_div_fmas_f32 v12, v12, v21, v14
	v_div_fixup_f32 v12, v12, v15, v17
	v_add_f32_e32 v14, 1.0, v16
	v_div_scale_f32 v16, s[8:9], v14, v14, v6
	v_rcp_f32_e32 v18, v16
	v_mul_f32_e32 v12, v12, v13
	v_mul_f32_e32 v15, 0xbfb8aa3b, v7
	v_cvt_pk_bf16_f32 v11, v11, v12
	v_fma_f32 v12, -v16, v18, 1.0
	v_exp_f32_e32 v15, v15
	v_fmac_f32_e32 v18, v12, v18
	v_div_scale_f32 v12, vcc, v6, v14, v6
	v_mul_f32_e32 v13, v12, v18
	v_fma_f32 v17, -v16, v13, v12
	v_fmac_f32_e32 v13, v17, v18
	v_add_f32_e32 v15, 1.0, v15
	v_fma_f32 v12, -v16, v13, v12
	v_div_scale_f32 v16, s[8:9], v15, v15, v7
	v_rcp_f32_e32 v17, v16
	v_div_fmas_f32 v12, v12, v18, v13
	v_div_fixup_f32 v6, v12, v14, v6
	v_mul_f32_e32 v2, v6, v2
	v_fma_f32 v6, -v16, v17, 1.0
	v_fmac_f32_e32 v17, v6, v17
	v_div_scale_f32 v6, vcc, v7, v15, v7
	v_mul_f32_e32 v12, v6, v17
	v_fma_f32 v13, -v16, v12, v6
	v_fmac_f32_e32 v12, v13, v17
	v_mul_f32_e32 v13, 0xbfb8aa3b, v8
	v_exp_f32_e32 v13, v13
	v_fma_f32 v6, -v16, v12, v6
	v_div_fmas_f32 v6, v6, v17, v12
	v_div_fixup_f32 v6, v6, v15, v7
	v_add_f32_e32 v13, 1.0, v13
	v_div_scale_f32 v14, s[8:9], v13, v13, v8
	v_rcp_f32_e32 v16, v14
	v_mul_f32_e32 v3, v6, v3
	v_mul_f32_e32 v6, 0xbfb8aa3b, v9
	v_exp_f32_e32 v6, v6
	v_cvt_pk_bf16_f32 v12, v2, v3
	v_fma_f32 v2, -v14, v16, 1.0
	v_fmac_f32_e32 v16, v2, v16
	v_div_scale_f32 v2, vcc, v8, v13, v8
	v_mul_f32_e32 v3, v2, v16
	v_fma_f32 v7, -v14, v3, v2
	v_add_f32_e32 v6, 1.0, v6
	v_fmac_f32_e32 v3, v7, v16
	v_div_scale_f32 v7, s[8:9], v6, v6, v9
	v_fma_f32 v2, -v14, v3, v2
	v_rcp_f32_e32 v14, v7
	v_div_fmas_f32 v2, v2, v16, v3
	v_div_fixup_f32 v2, v2, v13, v8
	v_mul_f32_e32 v2, v2, v4
	v_fma_f32 v3, -v7, v14, 1.0
	v_fmac_f32_e32 v14, v3, v14
	v_div_scale_f32 v3, vcc, v9, v6, v9
	v_mul_f32_e32 v4, v3, v14
	v_fma_f32 v8, -v7, v4, v3
	v_fmac_f32_e32 v4, v8, v14
	v_fma_f32 v3, -v7, v4, v3
	v_div_fmas_f32 v3, v3, v14, v4
	v_div_fixup_f32 v3, v3, v6, v9
	v_mul_f32_e32 v3, v3, v5
	v_add_u32_e32 v1, 0x40b0, v1
	v_cvt_pk_bf16_f32 v13, v2, v3
	v_mad_i64_i32 v[2:3], s[8:9], v1, s5, v[114:115]
	v_lshl_add_u64 v[2:3], v[2:3], 0, v[116:117]
	global_store_dwordx4 v[2:3], v[10:13], off
	s_waitcnt vmcnt(0)
	s_barrier
	s_waitcnt vmcnt(0)
	s_waitcnt vmcnt(0) lgkmcnt(0)
	s_barrier
	s_mov_b64 s[8:9], exec
	v_readlane_b32 s10, v228, 2
	v_readlane_b32 s11, v228, 3
	s_and_b64 s[10:11], s[8:9], s[10:11]
	s_mov_b64 exec, s[10:11]
	s_cbranch_execz .LBB0_5759
	s_mov_b64 s[10:11], exec
	v_mbcnt_lo_u32_b32 v1, s10, 0
	buffer_wbl2 sc1
	s_waitcnt vmcnt(0)
	v_mbcnt_hi_u32_b32 v1, s11, v1
	v_cmp_eq_u32_e32 vcc, 0, v1
	s_and_b64 s[12:13], exec, vcc
	s_mov_b64 exec, s[12:13]
	s_cbranch_execz .LBB0_5759
	s_bcnt1_i32_b64 s5, s[10:11]
	v_mov_b32_e32 v1, 0
	v_mov_b32_e32 v2, s5
	global_atomic_add v1, v2, s[6:7]

.LBB0_5775:
	s_add_u32 s6, s70, 0x7800000
	s_addc_u32 s7, s71, 0
	s_add_u32 s8, s70, 0x5c92000
	s_addc_u32 s9, s71, 0
	s_lshl_b32 s11, s24, 8
	s_add_i32 s10, s5, 0x4000
	v_lshl_or_b32 v130, v138, 2, s11
	v_or_b32_e32 v130, s35, v130
	v_or_b32_e32 v134, s10, v1
	s_movk_i32 s13, 0x4080
	s_movk_i32 s20, 0x4000
	s_ashr_i32 s12, s10, 13
	v_cmp_gt_i32_e32 vcc, s13, v134
	v_or_b32_e32 v132, 16, v130
	s_and_saveexec_b64 s[10:11], vcc
	s_cbranch_execz .LBB0_5777
	v_add_u32_e32 v131, 0xffffc002, v134
	v_mov_b32_e32 v133, s12
	v_cmp_gt_i32_e32 vcc, s20, v134
	s_mov_b32 s20, 0x9000
	v_mov_b64_e32 v[136:137], s[8:9]
	v_cndmask_b32_e32 v131, v131, v133, vcc
	v_mad_i64_i32 v[136:137], s[20:21], v131, s20, v[136:137]
	s_mov_b64 s[20:21], 0x8000
	v_ashrrev_i32_e32 v135, 31, v134
	v_lshl_add_u64 v[148:149], v[136:137], 0, s[20:21]
	v_lshlrev_b64 v[136:137], 12, v[134:135]
	v_add_u32_e32 v150, 0xffffc000, v134
	v_mov_b32_e32 v151, 0
	v_lshl_add_u64 v[144:145], s[6:7], 0, v[136:137]
	v_lshlrev_b64 v[136:137], 12, v[150:151]
	v_mov_b32_e32 v131, v151
	v_lshl_add_u64 v[136:137], s[14:15], 0, v[136:137]
	v_lshlrev_b64 v[146:147], 2, v[130:131]
	v_cndmask_b32_e32 v141, v137, v145, vcc
	v_cndmask_b32_e32 v140, v136, v144, vcc
	v_lshl_add_u64 v[136:137], v[148:149], 0, v[146:147]
	global_load_dwordx4 v[136:139], v[136:137], off
	v_lshl_add_u64 v[152:153], v[140:141], 0, v[146:147]
	global_load_dwordx4 v[140:143], v[152:153], off
	v_mov_b32_e32 v133, v151
	v_lshl_add_u64 v[154:155], v[144:145], 0, v[146:147]
	v_lshl_add_u64 v[144:145], v[132:133], 2, v[148:149]
	global_load_dwordx4 v[144:147], v[144:145], off
	v_or_b32_e32 v150, 0x80, v130
	s_waitcnt vmcnt(0) lgkmcnt(0)
	v_pk_mul_f32 v[128:129], v[128:129], v[138:139]
	v_pk_mul_f32 v[126:127], v[126:127], v[136:137]
	v_pk_fma_f32 v[128:129], v[128:129], 0.5, v[142:143] op_sel_hi:[1,0,1]
	v_pk_fma_f32 v[126:127], v[126:127], 0.5, v[140:141] op_sel_hi:[1,0,1]
	global_store_dwordx4 v[154:155], v[126:129], off
	global_load_dwordx4 v[126:129], v[152:153], off offset:64
	v_pk_mul_f32 v[124:125], v[124:125], v[146:147]
	v_pk_mul_f32 v[122:123], v[122:123], v[144:145]
	v_lshl_add_u64 v[136:137], v[150:151], 2, v[148:149]
	global_load_dwordx4 v[136:139], v[136:137], off
	v_or_b32_e32 v150, 0x90, v130
	s_waitcnt vmcnt(0) lgkmcnt(0)
	v_pk_fma_f32 v[124:125], v[124:125], 0.5, v[128:129] op_sel_hi:[1,0,1]
	v_pk_fma_f32 v[122:123], v[122:123], 0.5, v[126:127] op_sel_hi:[1,0,1]
	global_store_dwordx4 v[154:155], v[122:125], off offset:64
	global_load_dwordx4 v[122:125], v[152:153], off offset:512
	v_lshl_add_u64 v[126:127], v[150:151], 2, v[148:149]
	global_load_dwordx4 v[126:129], v[126:127], off
	v_pk_mul_f32 v[120:121], v[120:121], v[138:139]
	v_pk_mul_f32 v[118:119], v[118:119], v[136:137]
	s_waitcnt vmcnt(0) lgkmcnt(0)
	v_pk_fma_f32 v[120:121], v[120:121], 0.5, v[124:125] op_sel_hi:[1,0,1]
	v_pk_fma_f32 v[118:119], v[118:119], 0.5, v[122:123] op_sel_hi:[1,0,1]
	global_store_dwordx4 v[154:155], v[118:121], off offset:512
	global_load_dwordx4 v[118:121], v[152:153], off offset:576
	v_pk_mul_f32 v[116:117], v[116:117], v[128:129]
	v_pk_mul_f32 v[114:115], v[114:115], v[126:127]
	s_waitcnt vmcnt(0) lgkmcnt(0)
	v_pk_fma_f32 v[116:117], v[116:117], 0.5, v[120:121] op_sel_hi:[1,0,1]
	v_pk_fma_f32 v[114:115], v[114:115], 0.5, v[118:119] op_sel_hi:[1,0,1]
	global_store_dwordx4 v[154:155], v[114:117], off offset:576
.LBB0_5777:
	s_or_b64 exec, exec, s[10:11]
	s_nop 0
	v_or_b32_e32 v114, 16, v134
	v_cmp_gt_i32_e32 vcc, s13, v114
	s_and_saveexec_b64 s[10:11], vcc
	s_cbranch_execz .LBB0_5779
	s_movk_i32 s13, 0x4000
	v_add_u32_e32 v115, 0xffffc012, v134
	v_mov_b32_e32 v116, s12
	v_cmp_gt_i32_e32 vcc, s13, v114
	s_mov_b32 s13, 0x9000
	v_add_u32_e32 v128, 0xffffc010, v134
	v_cndmask_b32_e32 v115, v115, v116, vcc
	v_mov_b64_e32 v[116:117], s[8:9]
	v_mad_i64_i32 v[116:117], s[20:21], v115, s13, v[116:117]
	v_ashrrev_i32_e32 v115, 31, v114
	v_lshlrev_b64 v[114:115], 12, v[114:115]
	v_mov_b32_e32 v129, 0
	s_mov_b64 s[20:21], 0x8000
	v_lshl_add_u64 v[122:123], s[6:7], 0, v[114:115]
	v_lshlrev_b64 v[114:115], 12, v[128:129]
	v_mov_b32_e32 v131, v129
	v_lshl_add_u64 v[126:127], v[116:117], 0, s[20:21]
	v_lshl_add_u64 v[114:115], s[14:15], 0, v[114:115]
	v_lshlrev_b64 v[124:125], 2, v[130:131]
	v_cndmask_b32_e32 v119, v115, v123, vcc
	v_cndmask_b32_e32 v118, v114, v122, vcc
	v_lshl_add_u64 v[114:115], v[126:127], 0, v[124:125]
	global_load_dwordx4 v[114:117], v[114:115], off
	v_lshl_add_u64 v[136:137], v[118:119], 0, v[124:125]
	global_load_dwordx4 v[118:121], v[136:137], off
	v_mov_b32_e32 v133, v129
	v_lshl_add_u64 v[138:139], v[122:123], 0, v[124:125]
	v_lshl_add_u64 v[122:123], v[132:133], 2, v[126:127]
	global_load_dwordx4 v[122:125], v[122:123], off
	v_or_b32_e32 v128, 0x80, v130
	s_waitcnt vmcnt(0) lgkmcnt(0)
	v_pk_mul_f32 v[112:113], v[112:113], v[116:117]
	v_pk_mul_f32 v[110:111], v[110:111], v[114:115]
	v_pk_fma_f32 v[112:113], v[112:113], 0.5, v[120:121] op_sel_hi:[1,0,1]
	v_pk_fma_f32 v[110:111], v[110:111], 0.5, v[118:119] op_sel_hi:[1,0,1]
	global_store_dwordx4 v[138:139], v[110:113], off
	global_load_dwordx4 v[110:113], v[136:137], off offset:64
	v_pk_mul_f32 v[108:109], v[108:109], v[124:125]
	v_pk_mul_f32 v[106:107], v[106:107], v[122:123]
	v_lshl_add_u64 v[114:115], v[128:129], 2, v[126:127]
	global_load_dwordx4 v[114:117], v[114:115], off
	v_or_b32_e32 v128, 0x90, v130
	s_waitcnt vmcnt(0) lgkmcnt(0)
	v_pk_fma_f32 v[108:109], v[108:109], 0.5, v[112:113] op_sel_hi:[1,0,1]
	v_pk_fma_f32 v[106:107], v[106:107], 0.5, v[110:111] op_sel_hi:[1,0,1]
	global_store_dwordx4 v[138:139], v[106:109], off offset:64
	global_load_dwordx4 v[106:109], v[136:137], off offset:512
	v_lshl_add_u64 v[110:111], v[128:129], 2, v[126:127]
	global_load_dwordx4 v[110:113], v[110:111], off
	v_pk_mul_f32 v[104:105], v[104:105], v[116:117]
	v_pk_mul_f32 v[102:103], v[102:103], v[114:115]
	s_waitcnt vmcnt(0) lgkmcnt(0)
	v_pk_fma_f32 v[104:105], v[104:105], 0.5, v[108:109] op_sel_hi:[1,0,1]
	v_pk_fma_f32 v[102:103], v[102:103], 0.5, v[106:107] op_sel_hi:[1,0,1]
	global_store_dwordx4 v[138:139], v[102:105], off offset:512
	global_load_dwordx4 v[102:105], v[136:137], off offset:576
	v_pk_mul_f32 v[100:101], v[100:101], v[112:113]
	v_pk_mul_f32 v[98:99], v[98:99], v[110:111]
	s_waitcnt vmcnt(0) lgkmcnt(0)
	v_pk_fma_f32 v[100:101], v[100:101], 0.5, v[104:105] op_sel_hi:[1,0,1]
	v_pk_fma_f32 v[98:99], v[98:99], 0.5, v[102:103] op_sel_hi:[1,0,1]
	global_store_dwordx4 v[138:139], v[98:101], off offset:576
.LBB0_5779:
	s_or_b64 exec, exec, s[10:11]
	s_nop 0
	v_or_b32_e32 v98, 32, v134
	s_movk_i32 s13, 0x4080
	v_cmp_gt_i32_e32 vcc, s13, v98
	s_and_saveexec_b64 s[10:11], vcc
	s_cbranch_execz .LBB0_5781
	s_movk_i32 s20, 0x4000
	v_add_u32_e32 v99, 0xffffc022, v134
	v_mov_b32_e32 v100, s12
	v_cmp_gt_i32_e32 vcc, s20, v98
	s_mov_b32 s20, 0x9000
	v_add_u32_e32 v112, 0xffffc020, v134
	v_cndmask_b32_e32 v99, v99, v100, vcc
	v_mov_b64_e32 v[100:101], s[8:9]
	v_mad_i64_i32 v[100:101], s[20:21], v99, s20, v[100:101]
	v_ashrrev_i32_e32 v99, 31, v98
	v_lshlrev_b64 v[98:99], 12, v[98:99]
	v_mov_b32_e32 v113, 0
	s_mov_b64 s[20:21], 0x8000
	v_lshl_add_u64 v[106:107], s[6:7], 0, v[98:99]
	v_lshlrev_b64 v[98:99], 12, v[112:113]
	v_mov_b32_e32 v131, v113
	v_lshl_add_u64 v[110:111], v[100:101], 0, s[20:21]
	v_lshl_add_u64 v[98:99], s[14:15], 0, v[98:99]
	v_lshlrev_b64 v[108:109], 2, v[130:131]
	v_cndmask_b32_e32 v103, v99, v107, vcc
	v_cndmask_b32_e32 v102, v98, v106, vcc
	v_lshl_add_u64 v[98:99], v[110:111], 0, v[108:109]
	global_load_dwordx4 v[98:101], v[98:99], off
	v_lshl_add_u64 v[114:115], v[102:103], 0, v[108:109]
	global_load_dwordx4 v[102:105], v[114:115], off
	v_mov_b32_e32 v133, v113
	v_lshl_add_u64 v[116:117], v[106:107], 0, v[108:109]
	v_lshl_add_u64 v[106:107], v[132:133], 2, v[110:111]
	global_load_dwordx4 v[106:109], v[106:107], off
	v_or_b32_e32 v112, 0x80, v130
	s_waitcnt vmcnt(0) lgkmcnt(0)
	v_pk_mul_f32 v[96:97], v[96:97], v[100:101]
	v_pk_mul_f32 v[94:95], v[94:95], v[98:99]
	v_pk_fma_f32 v[96:97], v[96:97], 0.5, v[104:105] op_sel_hi:[1,0,1]
	v_pk_fma_f32 v[94:95], v[94:95], 0.5, v[102:103] op_sel_hi:[1,0,1]
	global_store_dwordx4 v[116:117], v[94:97], off
	global_load_dwordx4 v[94:97], v[114:115], off offset:64
	v_pk_mul_f32 v[92:93], v[92:93], v[108:109]
	v_pk_mul_f32 v[90:91], v[90:91], v[106:107]
	v_lshl_add_u64 v[98:99], v[112:113], 2, v[110:111]
	global_load_dwordx4 v[98:101], v[98:99], off
	v_or_b32_e32 v112, 0x90, v130
	s_waitcnt vmcnt(0) lgkmcnt(0)
	v_pk_fma_f32 v[92:93], v[92:93], 0.5, v[96:97] op_sel_hi:[1,0,1]
	v_pk_fma_f32 v[90:91], v[90:91], 0.5, v[94:95] op_sel_hi:[1,0,1]
	global_store_dwordx4 v[116:117], v[90:93], off offset:64
	global_load_dwordx4 v[90:93], v[114:115], off offset:512
	v_lshl_add_u64 v[94:95], v[112:113], 2, v[110:111]
	global_load_dwordx4 v[94:97], v[94:95], off
	v_pk_mul_f32 v[88:89], v[88:89], v[100:101]
	v_pk_mul_f32 v[86:87], v[86:87], v[98:99]
	s_waitcnt vmcnt(0) lgkmcnt(0)
	v_pk_fma_f32 v[88:89], v[88:89], 0.5, v[92:93] op_sel_hi:[1,0,1]
	v_pk_fma_f32 v[86:87], v[86:87], 0.5, v[90:91] op_sel_hi:[1,0,1]
	global_store_dwordx4 v[116:117], v[86:89], off offset:512
	global_load_dwordx4 v[86:89], v[114:115], off offset:576
	v_pk_mul_f32 v[84:85], v[84:85], v[96:97]
	v_pk_mul_f32 v[82:83], v[82:83], v[94:95]
	s_waitcnt vmcnt(0) lgkmcnt(0)
	v_pk_fma_f32 v[84:85], v[84:85], 0.5, v[88:89] op_sel_hi:[1,0,1]
	v_pk_fma_f32 v[82:83], v[82:83], 0.5, v[86:87] op_sel_hi:[1,0,1]
	global_store_dwordx4 v[116:117], v[82:85], off offset:576
.LBB0_5781:
	s_or_b64 exec, exec, s[10:11]
	s_nop 0
	v_or_b32_e32 v82, 48, v134
	v_cmp_gt_i32_e32 vcc, s13, v82
	s_and_saveexec_b64 s[10:11], vcc
	s_cbranch_execz .LBB0_5783
	s_movk_i32 s13, 0x4000
	v_add_u32_e32 v83, 0xffffc032, v134
	v_mov_b32_e32 v84, s12
	v_cmp_gt_i32_e32 vcc, s13, v82
	s_mov_b32 s12, 0x9000
	v_add_u32_e32 v96, 0xffffc030, v134
	v_cndmask_b32_e32 v83, v83, v84, vcc
	v_mov_b64_e32 v[84:85], s[8:9]
	v_mad_i64_i32 v[84:85], s[12:13], v83, s12, v[84:85]
	v_ashrrev_i32_e32 v83, 31, v82
	v_lshlrev_b64 v[82:83], 12, v[82:83]
	v_mov_b32_e32 v97, 0
	s_mov_b64 s[12:13], 0x8000
	v_lshl_add_u64 v[90:91], s[6:7], 0, v[82:83]
	v_lshlrev_b64 v[82:83], 12, v[96:97]
	v_mov_b32_e32 v131, v97
	v_lshl_add_u64 v[94:95], v[84:85], 0, s[12:13]
	v_lshl_add_u64 v[82:83], s[14:15], 0, v[82:83]
	v_lshlrev_b64 v[92:93], 2, v[130:131]
	v_cndmask_b32_e32 v87, v83, v91, vcc
	v_cndmask_b32_e32 v86, v82, v90, vcc
	v_lshl_add_u64 v[82:83], v[94:95], 0, v[92:93]
	global_load_dwordx4 v[82:85], v[82:83], off
	v_lshl_add_u64 v[98:99], v[86:87], 0, v[92:93]
	global_load_dwordx4 v[86:89], v[98:99], off
	v_mov_b32_e32 v133, v97
	v_lshl_add_u64 v[100:101], v[90:91], 0, v[92:93]
	v_lshl_add_u64 v[90:91], v[132:133], 2, v[94:95]
	global_load_dwordx4 v[90:93], v[90:91], off
	v_or_b32_e32 v96, 0x80, v130
	s_waitcnt vmcnt(0) lgkmcnt(0)
	v_pk_mul_f32 v[80:81], v[80:81], v[84:85]
	v_pk_mul_f32 v[78:79], v[78:79], v[82:83]
	v_pk_fma_f32 v[80:81], v[80:81], 0.5, v[88:89] op_sel_hi:[1,0,1]
	v_pk_fma_f32 v[78:79], v[78:79], 0.5, v[86:87] op_sel_hi:[1,0,1]
	global_store_dwordx4 v[100:101], v[78:81], off
	global_load_dwordx4 v[78:81], v[98:99], off offset:64
	v_pk_mul_f32 v[76:77], v[76:77], v[92:93]
	v_pk_mul_f32 v[74:75], v[74:75], v[90:91]
	v_lshl_add_u64 v[82:83], v[96:97], 2, v[94:95]
	global_load_dwordx4 v[82:85], v[82:83], off
	v_or_b32_e32 v96, 0x90, v130
	s_waitcnt vmcnt(0) lgkmcnt(0)
	v_pk_fma_f32 v[76:77], v[76:77], 0.5, v[80:81] op_sel_hi:[1,0,1]
	v_pk_fma_f32 v[74:75], v[74:75], 0.5, v[78:79] op_sel_hi:[1,0,1]
	global_store_dwordx4 v[100:101], v[74:77], off offset:64
	global_load_dwordx4 v[74:77], v[98:99], off offset:512
	v_lshl_add_u64 v[78:79], v[96:97], 2, v[94:95]
	global_load_dwordx4 v[78:81], v[78:79], off
	v_pk_mul_f32 v[72:73], v[72:73], v[84:85]
	v_pk_mul_f32 v[70:71], v[70:71], v[82:83]
	s_waitcnt vmcnt(0) lgkmcnt(0)
	v_pk_fma_f32 v[72:73], v[72:73], 0.5, v[76:77] op_sel_hi:[1,0,1]
	v_pk_fma_f32 v[70:71], v[70:71], 0.5, v[74:75] op_sel_hi:[1,0,1]
	global_store_dwordx4 v[100:101], v[70:73], off offset:512
	global_load_dwordx4 v[70:73], v[98:99], off offset:576
	v_pk_mul_f32 v[68:69], v[68:69], v[80:81]
	v_pk_mul_f32 v[66:67], v[66:67], v[78:79]
	s_waitcnt vmcnt(0) lgkmcnt(0)
	v_pk_fma_f32 v[68:69], v[68:69], 0.5, v[72:73] op_sel_hi:[1,0,1]
	v_pk_fma_f32 v[66:67], v[66:67], 0.5, v[70:71] op_sel_hi:[1,0,1]
	global_store_dwordx4 v[100:101], v[66:69], off offset:576
.LBB0_5783:
	s_or_b64 exec, exec, s[10:11]
	s_addk_i32 s5, 0x4080
	s_movk_i32 s12, 0x4080
	v_or_b32_e32 v66, s5, v1
	s_ashr_i32 s5, s5, 13
	v_cmp_gt_i32_e32 vcc, s12, v66
	s_and_saveexec_b64 s[10:11], vcc
	s_cbranch_execz .LBB0_5785
	s_movk_i32 s13, 0x4000
	v_add_u32_e32 v1, 0xffffc002, v66
	v_mov_b32_e32 v67, s5
	v_cmp_gt_i32_e32 vcc, s13, v66
	s_mov_b32 s13, 0x9000
	v_mov_b64_e32 v[68:69], s[8:9]
	v_cndmask_b32_e32 v1, v1, v67, vcc
	v_mad_i64_i32 v[68:69], s[20:21], v1, s13, v[68:69]
	s_mov_b64 s[20:21], 0x8000
	v_ashrrev_i32_e32 v67, 31, v66
	v_lshl_add_u64 v[80:81], v[68:69], 0, s[20:21]
	v_lshlrev_b64 v[68:69], 12, v[66:67]
	v_add_u32_e32 v82, 0xffffc000, v66
	v_mov_b32_e32 v83, 0
	v_lshl_add_u64 v[76:77], s[6:7], 0, v[68:69]
	v_lshlrev_b64 v[68:69], 12, v[82:83]
	v_mov_b32_e32 v131, v83
	v_lshl_add_u64 v[68:69], s[14:15], 0, v[68:69]
	v_lshlrev_b64 v[78:79], 2, v[130:131]
	v_cndmask_b32_e32 v73, v69, v77, vcc
	v_cndmask_b32_e32 v72, v68, v76, vcc
	v_lshl_add_u64 v[68:69], v[80:81], 0, v[78:79]
	global_load_dwordx4 v[68:71], v[68:69], off
	v_lshl_add_u64 v[84:85], v[72:73], 0, v[78:79]
	global_load_dwordx4 v[72:75], v[84:85], off
	v_mov_b32_e32 v133, v83
	v_lshl_add_u64 v[86:87], v[76:77], 0, v[78:79]
	v_lshl_add_u64 v[76:77], v[132:133], 2, v[80:81]
	global_load_dwordx4 v[76:79], v[76:77], off
	v_or_b32_e32 v82, 0x80, v130
	s_waitcnt vmcnt(0) lgkmcnt(0)
	v_pk_mul_f32 v[64:65], v[64:65], v[70:71]
	v_pk_mul_f32 v[62:63], v[62:63], v[68:69]
	v_pk_fma_f32 v[64:65], v[64:65], 0.5, v[74:75] op_sel_hi:[1,0,1]
	v_pk_fma_f32 v[62:63], v[62:63], 0.5, v[72:73] op_sel_hi:[1,0,1]
	global_store_dwordx4 v[86:87], v[62:65], off
	global_load_dwordx4 v[62:65], v[84:85], off offset:64
	v_pk_mul_f32 v[60:61], v[60:61], v[78:79]
	v_pk_mul_f32 v[58:59], v[58:59], v[76:77]
	v_lshl_add_u64 v[68:69], v[82:83], 2, v[80:81]
	global_load_dwordx4 v[68:71], v[68:69], off
	v_or_b32_e32 v82, 0x90, v130
	s_waitcnt vmcnt(0) lgkmcnt(0)
	v_pk_fma_f32 v[60:61], v[60:61], 0.5, v[64:65] op_sel_hi:[1,0,1]
	v_pk_fma_f32 v[58:59], v[58:59], 0.5, v[62:63] op_sel_hi:[1,0,1]
	global_store_dwordx4 v[86:87], v[58:61], off offset:64
	global_load_dwordx4 v[58:61], v[84:85], off offset:512
	v_lshl_add_u64 v[62:63], v[82:83], 2, v[80:81]
	global_load_dwordx4 v[62:65], v[62:63], off
	v_pk_mul_f32 v[56:57], v[56:57], v[70:71]
	v_pk_mul_f32 v[54:55], v[54:55], v[68:69]
	s_waitcnt vmcnt(0) lgkmcnt(0)
	v_pk_fma_f32 v[56:57], v[56:57], 0.5, v[60:61] op_sel_hi:[1,0,1]
	v_pk_fma_f32 v[54:55], v[54:55], 0.5, v[58:59] op_sel_hi:[1,0,1]
	global_store_dwordx4 v[86:87], v[54:57], off offset:512
	global_load_dwordx4 v[54:57], v[84:85], off offset:576
	v_pk_mul_f32 v[52:53], v[52:53], v[64:65]
	v_pk_mul_f32 v[50:51], v[50:51], v[62:63]
	s_waitcnt vmcnt(0) lgkmcnt(0)
	v_pk_fma_f32 v[52:53], v[52:53], 0.5, v[56:57] op_sel_hi:[1,0,1]
	v_pk_fma_f32 v[50:51], v[50:51], 0.5, v[54:55] op_sel_hi:[1,0,1]
	global_store_dwordx4 v[86:87], v[50:53], off offset:576
.LBB0_5785:
	s_or_b64 exec, exec, s[10:11]
	s_nop 0
	v_or_b32_e32 v50, 16, v66
	v_cmp_gt_i32_e32 vcc, s12, v50
	s_and_saveexec_b64 s[10:11], vcc
	s_cbranch_execz .LBB0_5787
	s_movk_i32 s12, 0x4000
	v_add_u32_e32 v1, 0xffffc012, v66
	v_mov_b32_e32 v51, s5
	v_cmp_gt_i32_e32 vcc, s12, v50
	s_mov_b32 s12, 0x9000
	v_mov_b64_e32 v[52:53], s[8:9]
	v_cndmask_b32_e32 v1, v1, v51, vcc
	v_ashrrev_i32_e32 v51, 31, v50
	v_mad_i64_i32 v[52:53], s[12:13], v1, s12, v[52:53]
	v_lshlrev_b64 v[50:51], 12, v[50:51]
	v_add_u32_e32 v64, 0xffffc010, v66
	v_mov_b32_e32 v65, 0
	s_mov_b64 s[12:13], 0x8000
	v_lshl_add_u64 v[58:59], s[6:7], 0, v[50:51]
	v_lshlrev_b64 v[50:51], 12, v[64:65]
	v_mov_b32_e32 v131, v65
	v_lshl_add_u64 v[62:63], v[52:53], 0, s[12:13]
	v_lshl_add_u64 v[50:51], s[14:15], 0, v[50:51]
	v_lshlrev_b64 v[60:61], 2, v[130:131]
	v_cndmask_b32_e32 v55, v51, v59, vcc
	v_cndmask_b32_e32 v54, v50, v58, vcc
	v_lshl_add_u64 v[50:51], v[62:63], 0, v[60:61]
	global_load_dwordx4 v[50:53], v[50:51], off
	v_lshl_add_u64 v[68:69], v[54:55], 0, v[60:61]
	global_load_dwordx4 v[54:57], v[68:69], off
	v_mov_b32_e32 v133, v65
	v_lshl_add_u64 v[70:71], v[58:59], 0, v[60:61]
	v_lshl_add_u64 v[58:59], v[132:133], 2, v[62:63]
	global_load_dwordx4 v[58:61], v[58:59], off
	v_or_b32_e32 v64, 0x80, v130
	s_waitcnt vmcnt(0) lgkmcnt(0)
	v_pk_mul_f32 v[48:49], v[48:49], v[52:53]
	v_pk_mul_f32 v[46:47], v[46:47], v[50:51]
	v_pk_fma_f32 v[48:49], v[48:49], 0.5, v[56:57] op_sel_hi:[1,0,1]
	v_pk_fma_f32 v[46:47], v[46:47], 0.5, v[54:55] op_sel_hi:[1,0,1]
	global_store_dwordx4 v[70:71], v[46:49], off
	global_load_dwordx4 v[46:49], v[68:69], off offset:64
	v_pk_mul_f32 v[44:45], v[44:45], v[60:61]
	v_pk_mul_f32 v[42:43], v[42:43], v[58:59]
	v_lshl_add_u64 v[50:51], v[64:65], 2, v[62:63]
	global_load_dwordx4 v[50:53], v[50:51], off
	v_or_b32_e32 v64, 0x90, v130
	s_waitcnt vmcnt(0) lgkmcnt(0)
	v_pk_fma_f32 v[44:45], v[44:45], 0.5, v[48:49] op_sel_hi:[1,0,1]
	v_pk_fma_f32 v[42:43], v[42:43], 0.5, v[46:47] op_sel_hi:[1,0,1]
	global_store_dwordx4 v[70:71], v[42:45], off offset:64
	global_load_dwordx4 v[42:45], v[68:69], off offset:512
	v_lshl_add_u64 v[46:47], v[64:65], 2, v[62:63]
	global_load_dwordx4 v[46:49], v[46:47], off
	v_pk_mul_f32 v[40:41], v[40:41], v[52:53]
	v_pk_mul_f32 v[38:39], v[38:39], v[50:51]
	s_waitcnt vmcnt(0) lgkmcnt(0)
	v_pk_fma_f32 v[40:41], v[40:41], 0.5, v[44:45] op_sel_hi:[1,0,1]
	v_pk_fma_f32 v[38:39], v[38:39], 0.5, v[42:43] op_sel_hi:[1,0,1]
	global_store_dwordx4 v[70:71], v[38:41], off offset:512
	global_load_dwordx4 v[38:41], v[68:69], off offset:576
	v_pk_mul_f32 v[36:37], v[36:37], v[48:49]
	v_pk_mul_f32 v[34:35], v[34:35], v[46:47]
	s_waitcnt vmcnt(0) lgkmcnt(0)
	v_pk_fma_f32 v[36:37], v[36:37], 0.5, v[40:41] op_sel_hi:[1,0,1]
	v_pk_fma_f32 v[34:35], v[34:35], 0.5, v[38:39] op_sel_hi:[1,0,1]
	global_store_dwordx4 v[70:71], v[34:37], off offset:576
.LBB0_5787:
	s_or_b64 exec, exec, s[10:11]
	s_nop 0
	v_or_b32_e32 v34, 32, v66
	s_movk_i32 s12, 0x4080
	v_cmp_gt_i32_e32 vcc, s12, v34
	s_and_saveexec_b64 s[10:11], vcc
	s_cbranch_execz .LBB0_5789
	s_movk_i32 s13, 0x4000
	v_add_u32_e32 v1, 0xffffc022, v66
	v_mov_b32_e32 v35, s5
	v_cmp_gt_i32_e32 vcc, s13, v34
	s_mov_b32 s13, 0x9000
	v_mov_b64_e32 v[36:37], s[8:9]
	v_cndmask_b32_e32 v1, v1, v35, vcc
	v_ashrrev_i32_e32 v35, 31, v34
	v_mad_i64_i32 v[36:37], s[20:21], v1, s13, v[36:37]
	v_lshlrev_b64 v[34:35], 12, v[34:35]
	v_add_u32_e32 v48, 0xffffc020, v66
	v_mov_b32_e32 v49, 0
	s_mov_b64 s[20:21], 0x8000
	v_lshl_add_u64 v[42:43], s[6:7], 0, v[34:35]
	v_lshlrev_b64 v[34:35], 12, v[48:49]
	v_mov_b32_e32 v131, v49
	v_lshl_add_u64 v[46:47], v[36:37], 0, s[20:21]
	v_lshl_add_u64 v[34:35], s[14:15], 0, v[34:35]
	v_lshlrev_b64 v[44:45], 2, v[130:131]
	v_cndmask_b32_e32 v39, v35, v43, vcc
	v_cndmask_b32_e32 v38, v34, v42, vcc
	v_lshl_add_u64 v[34:35], v[46:47], 0, v[44:45]
	global_load_dwordx4 v[34:37], v[34:35], off
	v_lshl_add_u64 v[50:51], v[38:39], 0, v[44:45]
	global_load_dwordx4 v[38:41], v[50:51], off
	v_mov_b32_e32 v133, v49
	v_lshl_add_u64 v[52:53], v[42:43], 0, v[44:45]
	v_lshl_add_u64 v[42:43], v[132:133], 2, v[46:47]
	global_load_dwordx4 v[42:45], v[42:43], off
	v_or_b32_e32 v48, 0x80, v130
	s_waitcnt vmcnt(0) lgkmcnt(0)
	v_pk_mul_f32 v[32:33], v[32:33], v[36:37]
	v_pk_mul_f32 v[30:31], v[30:31], v[34:35]
	v_pk_fma_f32 v[32:33], v[32:33], 0.5, v[40:41] op_sel_hi:[1,0,1]
	v_pk_fma_f32 v[30:31], v[30:31], 0.5, v[38:39] op_sel_hi:[1,0,1]
	global_store_dwordx4 v[52:53], v[30:33], off
	global_load_dwordx4 v[30:33], v[50:51], off offset:64
	v_pk_mul_f32 v[28:29], v[28:29], v[44:45]
	v_pk_mul_f32 v[26:27], v[26:27], v[42:43]
	v_lshl_add_u64 v[34:35], v[48:49], 2, v[46:47]
	global_load_dwordx4 v[34:37], v[34:35], off
	v_or_b32_e32 v48, 0x90, v130
	s_waitcnt vmcnt(0) lgkmcnt(0)
	v_pk_fma_f32 v[28:29], v[28:29], 0.5, v[32:33] op_sel_hi:[1,0,1]
	v_pk_fma_f32 v[26:27], v[26:27], 0.5, v[30:31] op_sel_hi:[1,0,1]
	global_store_dwordx4 v[52:53], v[26:29], off offset:64
	global_load_dwordx4 v[26:29], v[50:51], off offset:512
	v_lshl_add_u64 v[30:31], v[48:49], 2, v[46:47]
	global_load_dwordx4 v[30:33], v[30:31], off
	v_pk_mul_f32 v[24:25], v[24:25], v[36:37]
	v_pk_mul_f32 v[22:23], v[22:23], v[34:35]
	s_waitcnt vmcnt(0) lgkmcnt(0)
	v_pk_fma_f32 v[24:25], v[24:25], 0.5, v[28:29] op_sel_hi:[1,0,1]
	v_pk_fma_f32 v[22:23], v[22:23], 0.5, v[26:27] op_sel_hi:[1,0,1]
	global_store_dwordx4 v[52:53], v[22:25], off offset:512
	global_load_dwordx4 v[22:25], v[50:51], off offset:576
	v_pk_mul_f32 v[20:21], v[20:21], v[32:33]
	v_pk_mul_f32 v[18:19], v[18:19], v[30:31]
	s_waitcnt vmcnt(0) lgkmcnt(0)
	v_pk_fma_f32 v[20:21], v[20:21], 0.5, v[24:25] op_sel_hi:[1,0,1]
	v_pk_fma_f32 v[18:19], v[18:19], 0.5, v[22:23] op_sel_hi:[1,0,1]
	global_store_dwordx4 v[52:53], v[18:21], off offset:576
.LBB0_5789:
	s_or_b64 exec, exec, s[10:11]
	s_nop 0
	v_or_b32_e32 v18, 48, v66
	v_cmp_gt_i32_e32 vcc, s12, v18
	s_and_saveexec_b64 s[10:11], vcc
	s_cbranch_execz .LBB0_5791
	s_movk_i32 s12, 0x4000
	v_add_u32_e32 v1, 0xffffc032, v66
	v_mov_b32_e32 v19, s5
	v_cmp_gt_i32_e32 vcc, s12, v18
	s_mov_b32 s5, 0x9000
	v_mov_b64_e32 v[20:21], s[8:9]
	v_cndmask_b32_e32 v1, v1, v19, vcc
	v_ashrrev_i32_e32 v19, 31, v18
	v_mad_i64_i32 v[20:21], s[8:9], v1, s5, v[20:21]
	v_lshlrev_b64 v[18:19], 12, v[18:19]
	v_add_u32_e32 v32, 0xffffc030, v66
	v_mov_b32_e32 v33, 0
	s_mov_b64 s[8:9], 0x8000
	v_lshl_add_u64 v[26:27], s[6:7], 0, v[18:19]
	v_lshlrev_b64 v[18:19], 12, v[32:33]
	v_mov_b32_e32 v131, v33
	v_lshl_add_u64 v[30:31], v[20:21], 0, s[8:9]
	v_lshl_add_u64 v[18:19], s[14:15], 0, v[18:19]
	v_lshlrev_b64 v[28:29], 2, v[130:131]
	v_cndmask_b32_e32 v23, v19, v27, vcc
	v_cndmask_b32_e32 v22, v18, v26, vcc
	v_lshl_add_u64 v[18:19], v[30:31], 0, v[28:29]
	global_load_dwordx4 v[18:21], v[18:19], off
	v_lshl_add_u64 v[34:35], v[22:23], 0, v[28:29]
	global_load_dwordx4 v[22:25], v[34:35], off
	v_mov_b32_e32 v133, v33
	v_lshl_add_u64 v[36:37], v[26:27], 0, v[28:29]
	v_lshl_add_u64 v[26:27], v[132:133], 2, v[30:31]
	global_load_dwordx4 v[26:29], v[26:27], off
	v_or_b32_e32 v32, 0x80, v130
	s_waitcnt vmcnt(0) lgkmcnt(0)
	v_pk_mul_f32 v[16:17], v[16:17], v[20:21]
	v_pk_mul_f32 v[14:15], v[14:15], v[18:19]
	v_pk_fma_f32 v[16:17], v[16:17], 0.5, v[24:25] op_sel_hi:[1,0,1]
	v_pk_fma_f32 v[14:15], v[14:15], 0.5, v[22:23] op_sel_hi:[1,0,1]
	global_store_dwordx4 v[36:37], v[14:17], off
	global_load_dwordx4 v[14:17], v[34:35], off offset:64
	v_pk_mul_f32 v[12:13], v[12:13], v[28:29]
	v_pk_mul_f32 v[10:11], v[10:11], v[26:27]
	v_lshl_add_u64 v[18:19], v[32:33], 2, v[30:31]
	global_load_dwordx4 v[18:21], v[18:19], off
	v_or_b32_e32 v32, 0x90, v130
	s_waitcnt vmcnt(0) lgkmcnt(0)
	v_pk_fma_f32 v[12:13], v[12:13], 0.5, v[16:17] op_sel_hi:[1,0,1]
	v_pk_fma_f32 v[10:11], v[10:11], 0.5, v[14:15] op_sel_hi:[1,0,1]
	global_store_dwordx4 v[36:37], v[10:13], off offset:64
	global_load_dwordx4 v[10:13], v[34:35], off offset:512
	v_lshl_add_u64 v[14:15], v[32:33], 2, v[30:31]
	global_load_dwordx4 v[14:17], v[14:15], off
	v_pk_mul_f32 v[8:9], v[8:9], v[20:21]
	v_pk_mul_f32 v[6:7], v[6:7], v[18:19]
	s_waitcnt vmcnt(0) lgkmcnt(0)
	v_pk_fma_f32 v[8:9], v[8:9], 0.5, v[12:13] op_sel_hi:[1,0,1]
	v_pk_fma_f32 v[6:7], v[6:7], 0.5, v[10:11] op_sel_hi:[1,0,1]
	global_store_dwordx4 v[36:37], v[6:9], off offset:512
	global_load_dwordx4 v[6:9], v[34:35], off offset:576
	v_pk_mul_f32 v[4:5], v[4:5], v[16:17]
	v_pk_mul_f32 v[2:3], v[2:3], v[14:15]
	s_waitcnt vmcnt(0) lgkmcnt(0)
	v_pk_fma_f32 v[4:5], v[4:5], 0.5, v[8:9] op_sel_hi:[1,0,1]
	v_pk_fma_f32 v[2:3], v[2:3], 0.5, v[6:7] op_sel_hi:[1,0,1]
	global_store_dwordx4 v[36:37], v[2:5], off offset:576

.LBB0_5799:
	s_or_b64 exec, exec, s[6:7]
	v_mov_b32_e32 v1, v0
	v_mov_b64_e32 v[2:3], s[0:1]
	s_barrier
	global_load_dwordx2 v[2:3], v[2:3], off offset:200 sc0 sc1
	s_waitcnt vmcnt(0)
	v_readfirstlane_b32 s5, v1
	s_ashr_i32 s6, s5, 6
	s_cmp_gt_i32 s6, 7
	s_cbranch_scc1 .LBB0_5802
	v_and_b32_e32 v20, 63, v1
	v_mov_b32_e32 v83, 0
	v_lshlrev_b32_e32 v82, 4, v20
	s_waitcnt lgkmcnt(0)
	v_lshl_add_u64 v[18:19], v[2:3], 0, v[82:83]
	global_load_dwordx4 v[2:5], v[18:19], off
	global_load_dwordx4 v[6:9], v[18:19], off offset:1024
	global_load_dwordx4 v[10:13], v[18:19], off offset:2048
	global_load_dwordx4 v[14:17], v[18:19], off offset:3072
	v_mbcnt_lo_u32_b32 v1, -1, 0
	v_mbcnt_hi_u32_b32 v18, -1, v1
	v_and_b32_e32 v1, 64, v18
	v_add_u32_e32 v19, 64, v1
	v_xor_b32_e32 v1, 1, v18
	v_cmp_lt_i32_e32 vcc, v1, v19
	v_xor_b32_e32 v21, 2, v18
	s_lshl_b32 s7, s82, 5
	v_cndmask_b32_e32 v1, v18, v1, vcc
	v_cmp_lt_i32_e32 vcc, v21, v19
	s_lshl_b32 s6, s6, 2
	s_add_i32 s6, s7, s6
	v_cndmask_b32_e32 v21, v18, v21, vcc
	v_lshlrev_b32_e32 v94, 2, v21
	v_xor_b32_e32 v21, 4, v18
	v_cmp_lt_i32_e32 vcc, v21, v19
	s_add_i32 s5, s7, 0x20a0
	s_add_i32 s20, s6, 0x2080
	v_cndmask_b32_e32 v21, v18, v21, vcc
	v_lshlrev_b32_e32 v95, 2, v21
	v_xor_b32_e32 v21, 8, v18
	v_cmp_lt_i32_e32 vcc, v21, v19
	s_add_u32 s28, s68, 0x4000000
	s_addc_u32 s29, s69, 0
	v_cndmask_b32_e32 v21, v18, v21, vcc
	v_lshlrev_b32_e32 v96, 2, v21
	v_xor_b32_e32 v21, 16, v18
	v_cmp_lt_i32_e32 vcc, v21, v19
	s_ashr_i32 s21, s20, 31
	s_mov_b32 s23, 0
	v_cndmask_b32_e32 v21, v18, v21, vcc
	v_lshlrev_b32_e32 v97, 2, v21
	v_xor_b32_e32 v21, 32, v18
	v_cmp_lt_i32_e32 vcc, v21, v19
	v_lshlrev_b32_e32 v1, 2, v1
	s_lshl_b64 s[24:25], s[20:21], 12
	v_cndmask_b32_e32 v18, v18, v21, vcc
	v_lshlrev_b32_e32 v98, 2, v18
	v_lshlrev_b32_e32 v18, 2, v20
	v_lshl_add_u64 v[84:85], s[70:71], 0, v[82:83]
	v_mov_b32_e32 v99, 0x358637bd
	s_mov_b32 s21, 0xf800000
	v_mov_b32_e32 v100, 0x260
	v_lshlrev_b32_e32 v82, 2, v18
	s_mov_b64 s[26:27], 0x20000
	s_mov_b64 s[38:39], s[68:69]
.LBB0_5801:
	v_lshl_add_u64 v[18:19], v[84:85], 0, s[24:25]
	v_add_co_u32_e32 v20, vcc, 0x7800000, v18
	s_add_u32 s6, s38, s24
	s_nop 0
	v_addc_co_u32_e32 v21, vcc, 0, v19, vcc
	v_add_co_u32_e32 v22, vcc, 0x7801000, v18
	global_load_dwordx4 v[78:81], v[20:21], off
	global_load_dwordx4 v[70:73], v[20:21], off offset:1024
	global_load_dwordx4 v[66:69], v[20:21], off offset:3072
	global_load_dwordx4 v[74:77], v[20:21], off offset:2048
	v_addc_co_u32_e32 v23, vcc, 0, v19, vcc
	v_add_co_u32_e32 v20, vcc, 0x7802000, v18
	global_load_dwordx4 v[62:65], v[22:23], off
	global_load_dwordx4 v[54:57], v[22:23], off offset:1024
	global_load_dwordx4 v[50:53], v[22:23], off offset:3072
	global_load_dwordx4 v[58:61], v[22:23], off offset:2048
	v_addc_co_u32_e32 v21, vcc, 0, v19, vcc
	v_add_co_u32_e32 v86, vcc, 0x7803000, v18
	global_load_dwordx4 v[46:49], v[20:21], off
	global_load_dwordx4 v[42:45], v[20:21], off offset:1024
	global_load_dwordx4 v[38:41], v[20:21], off offset:2048
	global_load_dwordx4 v[34:37], v[20:21], off offset:3072
	v_addc_co_u32_e32 v87, vcc, 0, v19, vcc
	global_load_dwordx4 v[30:33], v[86:87], off
	global_load_dwordx4 v[26:29], v[86:87], off offset:1024
	global_load_dwordx4 v[22:25], v[86:87], off offset:2048
	global_load_dwordx4 v[18:21], v[86:87], off offset:3072
	s_addc_u32 s7, s39, s25
	s_add_i32 s22, s20, 0xffffc000
	s_lshl_b64 s[8:9], s[22:23], 12
	s_add_u32 s8, s28, s8
	s_addc_u32 s9, s29, s9
	s_cmpk_lt_i32 s20, 0x4000
	s_cselect_b32 s9, s7, s9
	s_cselect_b32 s8, s6, s8
	s_add_u32 s10, s6, 0x1000
	s_addc_u32 s11, s7, 0
	s_add_i32 s22, s20, 0xffffc001
	v_lshl_add_u64 v[92:93], s[8:9], 0, v[82:83]
	s_lshl_b64 s[8:9], s[22:23], 12
	s_add_u32 s8, s28, s8
	s_addc_u32 s9, s29, s9
	s_cmpk_lt_i32 s20, 0x3fff
	s_cselect_b32 s9, s11, s9
	s_cselect_b32 s8, s10, s8
	s_add_u32 s10, s6, 0x2000
	s_addc_u32 s11, s7, 0
	s_add_i32 s22, s20, 0xffffc002
	v_lshl_add_u64 v[90:91], s[8:9], 0, v[82:83]
	s_lshl_b64 s[8:9], s[22:23], 12
	s_add_u32 s8, s28, s8
	s_addc_u32 s9, s29, s9
	s_cmpk_lt_i32 s20, 0x3ffe
	s_cselect_b32 s9, s11, s9
	s_cselect_b32 s8, s10, s8
	s_add_u32 s10, s6, 0x3000
	v_lshl_add_u64 v[88:89], s[8:9], 0, v[82:83]
	s_addc_u32 s8, s7, 0
	s_add_i32 s22, s20, 0xffffc003
	s_lshl_b64 s[6:7], s[22:23], 12
	s_add_u32 s6, s28, s6
	s_addc_u32 s7, s29, s7
	s_cmpk_lt_i32 s20, 0x3ffd
	s_cselect_b32 s7, s8, s7
	s_cselect_b32 s6, s10, s6
	v_lshl_add_u64 v[86:87], s[6:7], 0, v[82:83]
	s_add_i32 s20, s20, 32
	s_add_u32 s38, s38, 0x20000
	s_addc_u32 s39, s39, 0
	v_lshl_add_u64 v[84:85], v[84:85], 0, s[26:27]
	s_cmp_lt_i32 s20, s5
	s_waitcnt vmcnt(0) lgkmcnt(0)
	v_pk_mul_f32 v[102:103], v[80:81], v[80:81]
	v_pk_mul_f32 v[104:105], v[78:79], v[78:79]
	v_pk_mul_f32 v[106:107], v[72:73], v[72:73]
	v_pk_mul_f32 v[108:109], v[70:71], v[70:71]
	v_mul_f32_e32 v110, v75, v75
	v_mul_f32_e32 v112, v77, v77
	v_pk_mov_b32 v[114:115], v[104:105], v[102:103] op_sel:[1,0]
	v_mov_b32_e32 v105, v103
	v_pk_mov_b32 v[102:103], v[108:109], v[106:107] op_sel:[1,0]
	v_mov_b32_e32 v109, v107
	v_mul_f32_e32 v123, v68, v68
	v_mul_f32_e32 v125, v69, v69
	v_pk_fma_f32 v[106:107], v[74:75], v[74:75], v[110:111] op_sel_hi:[1,1,0]
	v_pk_fma_f32 v[110:111], v[76:77], v[76:77], v[112:113] op_sel_hi:[1,1,0]
	v_pk_mul_f32 v[112:113], v[64:65], v[64:65]
	v_pk_mul_f32 v[116:117], v[62:63], v[62:63]
	v_pk_mul_f32 v[118:119], v[56:57], v[56:57]
	v_pk_mul_f32 v[120:121], v[54:55], v[54:55]
	v_mul_f32_e32 v122, v59, v59
	v_mul_f32_e32 v124, v61, v61
	v_pk_add_f32 v[104:105], v[114:115], v[104:105]
	v_pk_add_f32 v[102:103], v[102:103], v[108:109]
	v_mul_f32_e32 v101, v66, v66
	v_mul_f32_e32 v137, v67, v67
	v_mul_f32_e32 v131, v52, v52
	v_mul_f32_e32 v133, v53, v53
	v_mov_b32_e32 v107, v123
	v_mov_b32_e32 v111, v125
	v_pk_mov_b32 v[108:109], v[116:117], v[112:113] op_sel:[1,0]
	v_mov_b32_e32 v117, v113
	v_pk_mov_b32 v[112:113], v[120:121], v[118:119] op_sel:[1,0]
	v_mov_b32_e32 v121, v119
	v_pk_fma_f32 v[114:115], v[58:59], v[58:59], v[122:123] op_sel_hi:[1,1,0]
	v_pk_fma_f32 v[118:119], v[60:61], v[60:61], v[124:125] op_sel_hi:[1,1,0]
	v_pk_mul_f32 v[122:123], v[48:49], v[48:49]
	v_pk_mul_f32 v[124:125], v[46:47], v[46:47]
	v_pk_mul_f32 v[126:127], v[44:45], v[44:45]
	v_pk_mul_f32 v[128:129], v[42:43], v[42:43]
	v_mul_f32_e32 v130, v39, v39
	v_mul_f32_e32 v132, v41, v41
	v_pk_add_f32 v[104:105], v[104:105], v[104:105] op_sel:[0,1] op_sel_hi:[1,0]
	v_pk_add_f32 v[102:103], v[102:103], v[102:103] op_sel:[0,1] op_sel_hi:[1,0]
	v_mul_f32_e32 v143, v36, v36
	v_mul_f32_e32 v144, v37, v37
	v_pk_add_f32 v[106:107], v[106:107], v[110:111]
	v_pk_add_f32 v[108:109], v[108:109], v[116:117]
	v_pk_add_f32 v[110:111], v[112:113], v[120:121]
	v_mov_b32_e32 v115, v131
	v_mov_b32_e32 v119, v133
	v_pk_mov_b32 v[112:113], v[124:125], v[122:123] op_sel:[1,0]
	v_mov_b32_e32 v125, v123
	v_pk_mov_b32 v[116:117], v[128:129], v[126:127] op_sel:[1,0]
	v_mov_b32_e32 v129, v127
	v_pk_fma_f32 v[120:121], v[38:39], v[38:39], v[130:131] op_sel_hi:[1,1,0]
	v_pk_fma_f32 v[122:123], v[40:41], v[40:41], v[132:133] op_sel_hi:[1,1,0]
	v_pk_mul_f32 v[126:127], v[32:33], v[32:33]
	v_pk_mul_f32 v[130:131], v[30:31], v[30:31]
	v_pk_mul_f32 v[132:133], v[28:29], v[28:29]
	v_pk_mul_f32 v[134:135], v[26:27], v[26:27]
	v_mov_b32_e32 v105, v101
	v_mov_b32_e32 v103, v137
	v_mul_f32_e32 v139, v50, v50
	v_mul_f32_e32 v140, v51, v51
	v_pk_add_f32 v[108:109], v[108:109], v[108:109] op_sel:[0,1] op_sel_hi:[1,0]
	v_pk_add_f32 v[110:111], v[110:111], v[110:111] op_sel:[0,1] op_sel_hi:[1,0]
	v_pk_add_f32 v[114:115], v[114:115], v[118:119]
	v_pk_add_f32 v[112:113], v[112:113], v[124:125]
	v_pk_add_f32 v[116:117], v[116:117], v[128:129]
	v_mov_b32_e32 v121, v143
	v_mov_b32_e32 v123, v144
	v_pk_mov_b32 v[118:119], v[130:131], v[126:127] op_sel:[1,0]
	v_mov_b32_e32 v131, v127
	v_pk_mov_b32 v[124:125], v[134:135], v[132:133] op_sel:[1,0]
	v_mov_b32_e32 v135, v133
	v_pk_add_f32 v[102:103], v[104:105], v[102:103]
	v_mul_f32_e32 v141, v34, v34
	v_mul_f32_e32 v142, v35, v35
	v_mul_f32_e32 v136, v23, v23
	v_mul_f32_e32 v138, v25, v25
	v_mov_b32_e32 v109, v139
	v_mov_b32_e32 v111, v140
	v_pk_add_f32 v[104:105], v[112:113], v[112:113] op_sel:[0,1] op_sel_hi:[1,0]
	v_pk_add_f32 v[112:113], v[116:117], v[116:117] op_sel:[0,1] op_sel_hi:[1,0]
	v_pk_add_f32 v[116:117], v[120:121], v[122:123]
	v_pk_add_f32 v[118:119], v[118:119], v[130:131]
	v_pk_add_f32 v[120:121], v[124:125], v[134:135]
	v_pk_add_f32 v[102:103], v[102:103], v[106:107]
	v_mul_f32_e32 v145, v18, v18
	v_mul_f32_e32 v146, v19, v19
	v_mul_f32_e32 v147, v20, v20
	v_mul_f32_e32 v148, v21, v21
	v_pk_fma_f32 v[126:127], v[22:23], v[22:23], v[136:137] op_sel_hi:[1,1,0]
	v_pk_fma_f32 v[128:129], v[24:25], v[24:25], v[138:139] op_sel_hi:[1,1,0]
	v_pk_add_f32 v[106:107], v[108:109], v[110:111]
	v_mov_b32_e32 v105, v141
	v_mov_b32_e32 v113, v142
	v_pk_add_f32 v[108:109], v[118:119], v[118:119] op_sel:[0,1] op_sel_hi:[1,0]
	v_pk_add_f32 v[110:111], v[120:121], v[120:121] op_sel:[0,1] op_sel_hi:[1,0]
	v_add_f32_e32 v101, v102, v103
	v_mov_b32_e32 v127, v147
	v_mov_b32_e32 v129, v148
	v_pk_add_f32 v[102:103], v[106:107], v[114:115]
	v_pk_add_f32 v[104:105], v[104:105], v[112:113]
	v_mov_b32_e32 v109, v145
	v_mov_b32_e32 v111, v146
	ds_bpermute_b32 v107, v1, v101
	v_pk_add_f32 v[118:119], v[126:127], v[128:129]
	v_add_f32_e32 v106, v102, v103
	v_pk_add_f32 v[102:103], v[104:105], v[116:117]
	v_pk_add_f32 v[104:105], v[108:109], v[110:111]
	v_add_f32_e32 v108, v102, v103
	v_pk_add_f32 v[102:103], v[104:105], v[118:119]
	ds_bpermute_b32 v104, v1, v106
	v_add_f32_e32 v102, v102, v103
	ds_bpermute_b32 v103, v1, v108
	ds_bpermute_b32 v105, v1, v102
	s_waitcnt lgkmcnt(3)
	v_add_f32_e32 v101, v101, v107
	ds_bpermute_b32 v107, v94, v101
	s_waitcnt lgkmcnt(3)
	v_add_f32_e32 v104, v106, v104
	ds_bpermute_b32 v106, v94, v104
	s_waitcnt lgkmcnt(3)
	v_add_f32_e32 v103, v108, v103
	s_waitcnt lgkmcnt(2)
	v_add_f32_e32 v102, v102, v105
	ds_bpermute_b32 v108, v94, v103
	ds_bpermute_b32 v105, v94, v102
	s_waitcnt lgkmcnt(3)
	v_add_f32_e32 v101, v101, v107
	ds_bpermute_b32 v107, v95, v101
	s_waitcnt lgkmcnt(3)
	v_add_f32_e32 v104, v104, v106
	ds_bpermute_b32 v106, v95, v104
	s_waitcnt lgkmcnt(3)
	v_add_f32_e32 v103, v103, v108
	s_waitcnt lgkmcnt(2)
	v_add_f32_e32 v102, v102, v105
	ds_bpermute_b32 v108, v95, v103
	ds_bpermute_b32 v105, v95, v102
	s_waitcnt lgkmcnt(3)
	v_add_f32_e32 v101, v101, v107
	ds_bpermute_b32 v107, v96, v101
	s_waitcnt lgkmcnt(3)
	v_add_f32_e32 v104, v104, v106
	ds_bpermute_b32 v106, v96, v104
	s_waitcnt lgkmcnt(3)
	v_add_f32_e32 v103, v103, v108
	s_waitcnt lgkmcnt(2)
	v_add_f32_e32 v102, v102, v105
	ds_bpermute_b32 v108, v96, v103
	ds_bpermute_b32 v105, v96, v102
	s_waitcnt lgkmcnt(3)
	v_add_f32_e32 v101, v101, v107
	ds_bpermute_b32 v107, v97, v101
	s_waitcnt lgkmcnt(3)
	v_add_f32_e32 v104, v104, v106
	ds_bpermute_b32 v106, v97, v104
	s_waitcnt lgkmcnt(3)
	v_add_f32_e32 v103, v103, v108
	s_waitcnt lgkmcnt(2)
	v_add_f32_e32 v102, v102, v105
	ds_bpermute_b32 v108, v97, v103
	ds_bpermute_b32 v105, v97, v102
	s_waitcnt lgkmcnt(3)
	v_add_f32_e32 v101, v101, v107
	ds_bpermute_b32 v107, v98, v101
	s_waitcnt lgkmcnt(3)
	v_add_f32_e32 v104, v104, v106
	ds_bpermute_b32 v106, v98, v104
	s_waitcnt lgkmcnt(3)
	v_add_f32_e32 v103, v103, v108
	s_waitcnt lgkmcnt(2)
	v_add_f32_e32 v102, v102, v105
	ds_bpermute_b32 v108, v98, v103
	ds_bpermute_b32 v105, v98, v102
	s_waitcnt lgkmcnt(3)
	v_add_f32_e32 v101, v101, v107
	v_fmamk_f32 v101, v101, 0x3a800000, v99
	s_waitcnt lgkmcnt(2)
	v_add_f32_e32 v104, v104, v106
	v_mul_f32_e32 v106, 0x4f800000, v101
	v_cmp_gt_f32_e32 vcc, s21, v101
	v_fmamk_f32 v104, v104, 0x3a800000, v99
	s_waitcnt lgkmcnt(1)
	v_add_f32_e32 v103, v103, v108
	v_cndmask_b32_e32 v101, v101, v106, vcc
	v_mul_f32_e32 v106, 0x4f800000, v104
	v_cmp_gt_f32_e64 s[6:7], s21, v104
	s_waitcnt lgkmcnt(0)
	v_add_f32_e32 v102, v102, v105
	v_sqrt_f32_e32 v105, v101
	v_fmamk_f32 v103, v103, 0x3a800000, v99
	v_cndmask_b32_e64 v104, v104, v106, s[6:7]
	v_mul_f32_e32 v106, 0x4f800000, v103
	v_cmp_gt_f32_e64 s[8:9], s21, v103
	v_fmamk_f32 v102, v102, 0x3a800000, v99
	v_sqrt_f32_e32 v107, v104
	v_cndmask_b32_e64 v103, v103, v106, s[8:9]
	v_mul_f32_e32 v106, 0x4f800000, v102
	v_cmp_gt_f32_e64 s[10:11], s21, v102
	v_sqrt_f32_e32 v108, v103
	v_add_u32_e32 v109, -1, v105
	v_cndmask_b32_e64 v102, v102, v106, s[10:11]
	v_sqrt_f32_e32 v106, v102
	v_add_u32_e32 v110, 1, v105
	v_fma_f32 v111, -v109, v105, v101
	v_fma_f32 v112, -v110, v105, v101
	v_add_u32_e32 v113, -1, v107
	v_cmp_ge_f32_e64 s[12:13], 0, v111
	v_add_u32_e32 v114, 1, v107
	v_fma_f32 v111, -v114, v107, v104
	v_cndmask_b32_e64 v105, v105, v109, s[12:13]
	v_fma_f32 v109, -v113, v107, v104
	v_cmp_lt_f32_e64 s[12:13], 0, v112
	v_add_u32_e32 v115, -1, v108
	v_add_u32_e32 v116, 1, v108
	v_cndmask_b32_e64 v105, v105, v110, s[12:13]
	v_cmp_ge_f32_e64 s[12:13], 0, v109
	v_fma_f32 v109, -v115, v108, v103
	v_fma_f32 v110, -v116, v108, v103
	v_cndmask_b32_e64 v107, v107, v113, s[12:13]
	v_cmp_lt_f32_e64 s[12:13], 0, v111
	v_add_u32_e32 v111, -1, v106
	v_add_u32_e32 v112, 1, v106
	v_mul_f32_e32 v113, 0x37800000, v105
	v_cndmask_b32_e64 v107, v107, v114, s[12:13]
	v_cmp_ge_f32_e64 s[12:13], 0, v109
	v_fma_f32 v109, -v111, v106, v102
	v_cndmask_b32_e32 v105, v105, v113, vcc
	v_cndmask_b32_e64 v108, v108, v115, s[12:13]
	v_cmp_lt_f32_e64 s[12:13], 0, v110
	v_fma_f32 v110, -v112, v106, v102
	v_cmp_ge_f32_e32 vcc, 0, v109
	v_mul_f32_e32 v113, 0x37800000, v107
	v_cndmask_b32_e64 v108, v108, v116, s[12:13]
	v_cndmask_b32_e32 v106, v106, v111, vcc
	v_cmp_lt_f32_e32 vcc, 0, v110
	v_cmp_class_f32_e64 s[12:13], v101, v100
	s_nop 0
	v_cndmask_b32_e32 v106, v106, v112, vcc
	v_cndmask_b32_e64 v101, v105, v101, s[12:13]
	v_cndmask_b32_e64 v105, v107, v113, s[6:7]
	v_cmp_class_f32_e64 s[6:7], v104, v100
	v_mul_f32_e32 v107, 0x37800000, v108
	v_div_scale_f32 v109, s[12:13], v101, v101, 1.0
	v_cndmask_b32_e64 v111, v105, v104, s[6:7]
	v_cndmask_b32_e64 v104, v108, v107, s[8:9]
	v_cmp_class_f32_e64 s[6:7], v103, v100
	v_mul_f32_e32 v105, 0x37800000, v106
	v_rcp_f32_e32 v107, v109
	v_div_scale_f32 v108, s[8:9], v111, v111, 1.0
	v_cndmask_b32_e64 v113, v104, v103, s[6:7]
	v_cndmask_b32_e64 v103, v106, v105, s[10:11]
	v_cmp_class_f32_e64 s[6:7], v102, v100
	v_rcp_f32_e32 v104, v108
	v_div_scale_f32 v105, s[10:11], v113, v113, 1.0
	v_cndmask_b32_e64 v114, v103, v102, s[6:7]
	v_rcp_f32_e32 v115, v105
	v_div_scale_f32 v116, s[6:7], v114, v114, 1.0
	v_rcp_f32_e32 v118, v116
	v_fma_f32 v102, -v109, v107, 1.0
	v_div_scale_f32 v110, vcc, 1.0, v101, 1.0
	v_fmac_f32_e32 v107, v102, v107
	v_fma_f32 v102, -v108, v104, 1.0
	v_div_scale_f32 v112, s[8:9], 1.0, v111, 1.0
	v_mul_f32_e32 v103, v110, v107
	v_fmac_f32_e32 v104, v102, v104
	v_fma_f32 v102, -v105, v115, 1.0
	v_div_scale_f32 v106, s[10:11], 1.0, v113, 1.0
	v_fma_f32 v119, -v109, v103, v110
	v_mul_f32_e32 v120, v112, v104
	v_fmac_f32_e32 v115, v102, v115
	v_fma_f32 v102, -v116, v118, 1.0
	v_div_scale_f32 v117, s[6:7], 1.0, v114, 1.0
	v_fmac_f32_e32 v103, v119, v107
	v_fma_f32 v119, -v108, v120, v112
	v_mul_f32_e32 v121, v106, v115
	v_fmac_f32_e32 v118, v102, v118
	v_fma_f32 v102, -v109, v103, v110
	v_fmac_f32_e32 v120, v119, v104
	v_fma_f32 v109, -v105, v121, v106
	v_mul_f32_e32 v110, v117, v118
	v_div_fmas_f32 v102, v102, v107, v103
	v_fma_f32 v103, -v108, v120, v112
	v_fmac_f32_e32 v121, v109, v115
	v_fma_f32 v107, -v116, v110, v117
	s_mov_b64 vcc, s[8:9]
	v_div_fixup_f32 v102, v102, v101, 1.0
	v_div_fmas_f32 v101, v103, v104, v120
	v_fma_f32 v108, -v105, v121, v106
	v_fmac_f32_e32 v110, v107, v118
	s_mov_b64 vcc, s[10:11]
	v_pk_mul_f32 v[78:79], v[78:79], v[102:103] op_sel_hi:[1,0]
	v_pk_mul_f32 v[80:81], v[80:81], v[102:103] op_sel_hi:[1,0]
	v_pk_mul_f32 v[70:71], v[70:71], v[102:103] op_sel_hi:[1,0]
	v_pk_mul_f32 v[72:73], v[72:73], v[102:103] op_sel_hi:[1,0]
	v_pk_mul_f32 v[74:75], v[74:75], v[102:103] op_sel_hi:[1,0]
	v_pk_mul_f32 v[76:77], v[76:77], v[102:103] op_sel_hi:[1,0]
	v_pk_mul_f32 v[104:105], v[66:67], v[102:103] op_sel_hi:[1,0]
	v_pk_mul_f32 v[102:103], v[68:69], v[102:103] op_sel_hi:[1,0]
	v_div_fixup_f32 v106, v101, v111, 1.0
	v_div_fmas_f32 v101, v108, v115, v121
	v_fma_f32 v107, -v116, v110, v117
	s_mov_b64 vcc, s[6:7]
	v_pk_mul_f32 v[68:69], v[80:81], v[4:5]
	v_pk_mul_f32 v[66:67], v[78:79], v[2:3]
	v_pk_mul_f32 v[74:75], v[74:75], v[10:11]
	v_pk_mul_f32 v[80:81], v[102:103], v[16:17]
	v_pk_mul_f32 v[78:79], v[104:105], v[14:15]
	v_pk_mul_f32 v[62:63], v[62:63], v[106:107] op_sel_hi:[1,0]
	v_pk_mul_f32 v[64:65], v[64:65], v[106:107] op_sel_hi:[1,0]
	v_pk_mul_f32 v[54:55], v[54:55], v[106:107] op_sel_hi:[1,0]
	v_pk_mul_f32 v[56:57], v[56:57], v[106:107] op_sel_hi:[1,0]
	v_pk_mul_f32 v[58:59], v[58:59], v[106:107] op_sel_hi:[1,0]
	v_pk_mul_f32 v[60:61], v[60:61], v[106:107] op_sel_hi:[1,0]
	v_pk_mul_f32 v[102:103], v[50:51], v[106:107] op_sel_hi:[1,0]
	v_pk_mul_f32 v[104:105], v[52:53], v[106:107] op_sel_hi:[1,0]
	v_div_fixup_f32 v106, v101, v113, 1.0
	v_div_fmas_f32 v101, v107, v118, v110
	v_pk_mul_f32 v[72:73], v[72:73], v[8:9]
	v_pk_mul_f32 v[70:71], v[70:71], v[6:7]
	v_pk_mul_f32 v[76:77], v[76:77], v[12:13]
	global_store_dwordx4 v[92:93], v[66:69], off
	global_store_dwordx4 v[92:93], v[70:73], off offset:1024
	global_store_dwordx4 v[92:93], v[74:77], off offset:2048
	global_store_dwordx4 v[92:93], v[78:81], off offset:3072
	v_pk_mul_f32 v[52:53], v[64:65], v[4:5]
	v_div_fixup_f32 v74, v101, v114, 1.0
	v_pk_mul_f32 v[50:51], v[62:63], v[2:3]
	v_pk_mul_f32 v[56:57], v[56:57], v[8:9]
	v_pk_mul_f32 v[54:55], v[54:55], v[6:7]
	v_pk_mul_f32 v[46:47], v[46:47], v[106:107] op_sel_hi:[1,0]
	v_pk_mul_f32 v[48:49], v[48:49], v[106:107] op_sel_hi:[1,0]
	v_pk_mul_f32 v[30:31], v[30:31], v[74:75] op_sel_hi:[1,0]
	v_pk_mul_f32 v[32:33], v[32:33], v[74:75] op_sel_hi:[1,0]
	v_pk_mul_f32 v[60:61], v[60:61], v[12:13]
	v_pk_mul_f32 v[58:59], v[58:59], v[10:11]
	v_pk_mul_f32 v[64:65], v[104:105], v[16:17]
	v_pk_mul_f32 v[62:63], v[102:103], v[14:15]
	v_pk_mul_f32 v[42:43], v[42:43], v[106:107] op_sel_hi:[1,0]
	v_pk_mul_f32 v[44:45], v[44:45], v[106:107] op_sel_hi:[1,0]
	v_pk_mul_f32 v[66:67], v[38:39], v[106:107] op_sel_hi:[1,0]
	v_pk_mul_f32 v[68:69], v[40:41], v[106:107] op_sel_hi:[1,0]
	v_pk_mul_f32 v[70:71], v[34:35], v[106:107] op_sel_hi:[1,0]
	v_pk_mul_f32 v[72:73], v[36:37], v[106:107] op_sel_hi:[1,0]
	global_store_dwordx4 v[90:91], v[50:53], off
	global_store_dwordx4 v[90:91], v[54:57], off offset:1024
	global_store_dwordx4 v[90:91], v[58:61], off offset:2048
	global_store_dwordx4 v[90:91], v[62:65], off offset:3072
	v_pk_mul_f32 v[36:37], v[48:49], v[4:5]
	v_pk_mul_f32 v[34:35], v[46:47], v[2:3]
	v_pk_mul_f32 v[26:27], v[26:27], v[74:75] op_sel_hi:[1,0]
	v_pk_mul_f32 v[28:29], v[28:29], v[74:75] op_sel_hi:[1,0]
	v_pk_mul_f32 v[50:51], v[22:23], v[74:75] op_sel_hi:[1,0]
	v_pk_mul_f32 v[52:53], v[24:25], v[74:75] op_sel_hi:[1,0]
	v_pk_mul_f32 v[54:55], v[18:19], v[74:75] op_sel_hi:[1,0]
	v_pk_mul_f32 v[56:57], v[20:21], v[74:75] op_sel_hi:[1,0]
	v_pk_mul_f32 v[20:21], v[32:33], v[4:5]
	v_pk_mul_f32 v[18:19], v[30:31], v[2:3]
	v_pk_mul_f32 v[40:41], v[44:45], v[8:9]
	v_pk_mul_f32 v[38:39], v[42:43], v[6:7]
	v_pk_mul_f32 v[44:45], v[68:69], v[12:13]
	v_pk_mul_f32 v[42:43], v[66:67], v[10:11]
	v_pk_mul_f32 v[48:49], v[72:73], v[16:17]
	v_pk_mul_f32 v[46:47], v[70:71], v[14:15]
	global_store_dwordx4 v[88:89], v[34:37], off
	global_store_dwordx4 v[88:89], v[38:41], off offset:1024
	global_store_dwordx4 v[88:89], v[42:45], off offset:2048
	global_store_dwordx4 v[88:89], v[46:49], off offset:3072
	v_pk_mul_f32 v[24:25], v[28:29], v[8:9]
	v_pk_mul_f32 v[22:23], v[26:27], v[6:7]
	v_pk_mul_f32 v[28:29], v[52:53], v[12:13]
	v_pk_mul_f32 v[26:27], v[50:51], v[10:11]
	v_pk_mul_f32 v[32:33], v[56:57], v[16:17]
	v_pk_mul_f32 v[30:31], v[54:55], v[14:15]
	global_store_dwordx4 v[86:87], v[18:21], off
	global_store_dwordx4 v[86:87], v[22:25], off offset:1024
	global_store_dwordx4 v[86:87], v[26:29], off offset:2048
	global_store_dwordx4 v[86:87], v[30:33], off offset:3072
	s_cbranch_scc1 .LBB0_5801

.LBB0_5822:
	v_mul_f32_e32 v148, 0xbfb8aa3b, v126
	v_exp_f32_e32 v149, v148
	v_lshl_add_u32 v148, s42, 8, v1
	v_lshl_or_b32 v150, s43, 7, v142
	v_mul_f32_e32 v156, 0xbfb8aa3b, v127
	v_add_f32_e32 v149, 1.0, v149
	v_div_scale_f32 v152, s[42:43], v149, v149, v126
	v_rcp_f32_e32 v153, v152
	v_div_scale_f32 v154, vcc, v126, v149, v126
	v_exp_f32_e32 v156, v156
	v_fma_f32 v155, -v152, v153, 1.0
	v_fmac_f32_e32 v153, v155, v153
	v_mul_f32_e32 v155, v154, v153
	v_fma_f32 v157, -v152, v155, v154
	v_fmac_f32_e32 v155, v157, v153
	v_fma_f32 v152, -v152, v155, v154
	v_add_f32_e32 v154, 1.0, v156
	v_div_scale_f32 v156, s[42:43], v154, v154, v127
	v_rcp_f32_e32 v157, v156
	v_div_fmas_f32 v152, v152, v153, v155
	v_div_fixup_f32 v126, v152, v149, v126
	v_mul_f32_e32 v122, v126, v122
	v_fma_f32 v126, -v156, v157, 1.0
	v_fmac_f32_e32 v157, v126, v157
	v_div_scale_f32 v126, vcc, v127, v154, v127
	v_mul_f32_e32 v149, v126, v157
	v_fma_f32 v152, -v156, v149, v126
	v_fmac_f32_e32 v149, v152, v157
	v_mul_f32_e32 v152, 0xbfb8aa3b, v128
	v_exp_f32_e32 v152, v152
	v_fma_f32 v126, -v156, v149, v126
	v_div_fmas_f32 v126, v126, v157, v149
	v_div_fixup_f32 v126, v126, v154, v127
	v_add_f32_e32 v149, 1.0, v152
	v_div_scale_f32 v152, s[42:43], v149, v149, v128
	v_rcp_f32_e32 v153, v152
	v_mul_f32_e32 v123, v126, v123
	v_mul_f32_e32 v127, 0xbfb8aa3b, v129
	v_cvt_pk_bf16_f32 v122, v122, v123
	v_fma_f32 v123, -v152, v153, 1.0
	v_exp_f32_e32 v127, v127
	v_fmac_f32_e32 v153, v123, v153
	v_div_scale_f32 v123, vcc, v128, v149, v128
	v_mul_f32_e32 v126, v123, v153
	v_fma_f32 v154, -v152, v126, v123
	v_fmac_f32_e32 v126, v154, v153
	v_add_f32_e32 v127, 1.0, v127
	v_fma_f32 v123, -v152, v126, v123
	v_div_scale_f32 v152, s[42:43], v127, v127, v129
	v_rcp_f32_e32 v154, v152
	v_div_fmas_f32 v123, v123, v153, v126
	v_div_fixup_f32 v123, v123, v149, v128
	v_mul_f32_e32 v123, v123, v124
	v_fma_f32 v124, -v152, v154, 1.0
	v_fmac_f32_e32 v154, v124, v154
	v_div_scale_f32 v124, vcc, v129, v127, v129
	v_mul_f32_e32 v126, v124, v154
	v_fma_f32 v128, -v152, v126, v124
	v_fmac_f32_e32 v126, v128, v154
	v_mul_f32_e32 v128, 0xbfb8aa3b, v118
	v_exp_f32_e32 v128, v128
	v_fma_f32 v124, -v152, v126, v124
	v_div_fmas_f32 v124, v124, v154, v126
	v_div_fixup_f32 v124, v124, v127, v129
	v_add_f32_e32 v126, 1.0, v128
	v_div_scale_f32 v128, s[42:43], v126, v126, v118
	v_rcp_f32_e32 v149, v128
	v_mul_f32_e32 v124, v124, v125
	v_mul_f32_e32 v127, 0xbfb8aa3b, v119
	v_cvt_pk_bf16_f32 v123, v123, v124
	v_fma_f32 v124, -v128, v149, 1.0
	v_exp_f32_e32 v127, v127
	v_fmac_f32_e32 v149, v124, v149
	v_div_scale_f32 v124, vcc, v118, v126, v118
	v_mul_f32_e32 v125, v124, v149
	v_fma_f32 v129, -v128, v125, v124
	v_fmac_f32_e32 v125, v129, v149
	v_add_f32_e32 v127, 1.0, v127
	v_fma_f32 v124, -v128, v125, v124
	v_div_scale_f32 v128, s[42:43], v127, v127, v119
	v_rcp_f32_e32 v129, v128
	v_div_fmas_f32 v124, v124, v149, v125
	v_div_fixup_f32 v118, v124, v126, v118
	v_mul_f32_e32 v114, v118, v114
	v_fma_f32 v118, -v128, v129, 1.0
	v_fmac_f32_e32 v129, v118, v129
	v_div_scale_f32 v118, vcc, v119, v127, v119
	v_mul_f32_e32 v124, v118, v129
	v_fma_f32 v125, -v128, v124, v118
	v_fmac_f32_e32 v124, v125, v129
	v_mul_f32_e32 v125, 0xbfb8aa3b, v120
	v_exp_f32_e32 v125, v125
	v_fma_f32 v118, -v128, v124, v118
	v_div_fmas_f32 v118, v118, v129, v124
	v_div_fixup_f32 v118, v118, v127, v119
	v_add_f32_e32 v125, 1.0, v125
	v_div_scale_f32 v126, s[42:43], v125, v125, v120
	v_rcp_f32_e32 v128, v126
	v_mul_f32_e32 v115, v118, v115
	v_mul_f32_e32 v118, 0xbfb8aa3b, v121
	v_exp_f32_e32 v118, v118
	v_cvt_pk_bf16_f32 v124, v114, v115
	v_fma_f32 v114, -v126, v128, 1.0
	v_fmac_f32_e32 v128, v114, v128
	v_div_scale_f32 v114, vcc, v120, v125, v120
	v_mul_f32_e32 v115, v114, v128
	v_fma_f32 v119, -v126, v115, v114
	v_add_f32_e32 v118, 1.0, v118
	v_fmac_f32_e32 v115, v119, v128
	v_div_scale_f32 v119, s[42:43], v118, v118, v121
	v_fma_f32 v114, -v126, v115, v114
	v_rcp_f32_e32 v126, v119
	v_div_fmas_f32 v114, v114, v128, v115
	v_div_fixup_f32 v114, v114, v125, v120
	v_mul_f32_e32 v114, v114, v116
	v_fma_f32 v115, -v119, v126, 1.0
	v_fmac_f32_e32 v126, v115, v126
	v_div_scale_f32 v115, vcc, v121, v118, v121
	v_mul_f32_e32 v116, v115, v126
	v_fma_f32 v120, -v119, v116, v115
	v_fmac_f32_e32 v116, v120, v126
	v_fma_f32 v115, -v119, v116, v115
	v_div_fmas_f32 v115, v115, v126, v116
	v_div_fixup_f32 v115, v115, v118, v121
	v_mul_f32_e32 v115, v115, v117
	v_cvt_pk_bf16_f32 v125, v114, v115
	v_mul_f32_e32 v114, 0xbfb8aa3b, v110
	v_exp_f32_e32 v116, v114
	v_ashrrev_i32_e32 v151, 31, v150
	v_mov_b64_e32 v[114:115], s[18:19]
	v_mad_i64_i32 v[118:119], s[42:43], v148, s59, v[114:115]
	v_add_f32_e32 v120, 1.0, v116
	v_div_scale_f32 v121, s[42:43], v120, v120, v110
	v_rcp_f32_e32 v126, v121
	v_lshlrev_b64 v[116:117], 1, v[150:151]
	v_lshl_add_u64 v[118:119], v[118:119], 0, v[116:117]
	global_store_dwordx4 v[118:119], v[122:125], off
	v_fma_f32 v118, -v121, v126, 1.0
	v_fmac_f32_e32 v126, v118, v126
	v_mul_f32_e32 v122, 0xbfb8aa3b, v111
	v_div_scale_f32 v118, vcc, v110, v120, v110
	v_exp_f32_e32 v122, v122
	v_mul_f32_e32 v119, v118, v126
	v_fma_f32 v123, -v121, v119, v118
	v_fmac_f32_e32 v119, v123, v126
	v_fma_f32 v118, -v121, v119, v118
	v_add_f32_e32 v121, 1.0, v122
	v_div_scale_f32 v122, s[42:43], v121, v121, v111
	v_rcp_f32_e32 v123, v122
	v_div_fmas_f32 v118, v118, v126, v119
	v_div_fixup_f32 v110, v118, v120, v110
	v_mul_f32_e32 v106, v110, v106
	v_fma_f32 v110, -v122, v123, 1.0
	v_fmac_f32_e32 v123, v110, v123
	v_div_scale_f32 v110, vcc, v111, v121, v111
	v_mul_f32_e32 v118, v110, v123
	v_fma_f32 v119, -v122, v118, v110
	v_fmac_f32_e32 v118, v119, v123
	v_mul_f32_e32 v119, 0xbfb8aa3b, v112
	v_exp_f32_e32 v119, v119
	v_fma_f32 v110, -v122, v118, v110
	v_div_fmas_f32 v110, v110, v123, v118
	v_div_fixup_f32 v110, v110, v121, v111
	v_add_f32_e32 v118, 1.0, v119
	v_div_scale_f32 v119, s[42:43], v118, v118, v112
	v_rcp_f32_e32 v120, v119
	v_mul_f32_e32 v107, v110, v107
	v_mul_f32_e32 v111, 0xbfb8aa3b, v113
	v_cvt_pk_bf16_f32 v106, v106, v107
	v_fma_f32 v107, -v119, v120, 1.0
	v_exp_f32_e32 v111, v111
	v_fmac_f32_e32 v120, v107, v120
	v_div_scale_f32 v107, vcc, v112, v118, v112
	v_mul_f32_e32 v110, v107, v120
	v_fma_f32 v121, -v119, v110, v107
	v_fmac_f32_e32 v110, v121, v120
	v_add_f32_e32 v111, 1.0, v111
	v_fma_f32 v107, -v119, v110, v107
	v_div_scale_f32 v119, s[42:43], v111, v111, v113
	v_rcp_f32_e32 v121, v119
	v_div_fmas_f32 v107, v107, v120, v110
	v_div_fixup_f32 v107, v107, v118, v112
	v_mul_f32_e32 v107, v107, v108
	v_fma_f32 v108, -v119, v121, 1.0
	v_fmac_f32_e32 v121, v108, v121
	v_div_scale_f32 v108, vcc, v113, v111, v113
	v_mul_f32_e32 v110, v108, v121
	v_fma_f32 v112, -v119, v110, v108
	v_fmac_f32_e32 v110, v112, v121
	v_mul_f32_e32 v112, 0xbfb8aa3b, v102
	v_exp_f32_e32 v112, v112
	v_fma_f32 v108, -v119, v110, v108
	v_div_fmas_f32 v108, v108, v121, v110
	v_div_fixup_f32 v108, v108, v111, v113
	v_add_f32_e32 v110, 1.0, v112
	v_div_scale_f32 v112, s[42:43], v110, v110, v102
	v_rcp_f32_e32 v118, v112
	v_mul_f32_e32 v108, v108, v109
	v_mul_f32_e32 v111, 0xbfb8aa3b, v103
	v_cvt_pk_bf16_f32 v107, v107, v108
	v_fma_f32 v108, -v112, v118, 1.0
	v_exp_f32_e32 v111, v111
	v_fmac_f32_e32 v118, v108, v118
	v_div_scale_f32 v108, vcc, v102, v110, v102
	v_mul_f32_e32 v109, v108, v118
	v_fma_f32 v113, -v112, v109, v108
	v_fmac_f32_e32 v109, v113, v118
	v_add_f32_e32 v111, 1.0, v111
	v_fma_f32 v108, -v112, v109, v108
	v_div_scale_f32 v112, s[42:43], v111, v111, v103
	v_rcp_f32_e32 v113, v112
	v_div_fmas_f32 v108, v108, v118, v109
	v_div_fixup_f32 v102, v108, v110, v102
	v_mul_f32_e32 v98, v102, v98
	v_fma_f32 v102, -v112, v113, 1.0
	v_fmac_f32_e32 v113, v102, v113
	v_div_scale_f32 v102, vcc, v103, v111, v103
	v_mul_f32_e32 v108, v102, v113
	v_fma_f32 v109, -v112, v108, v102
	v_fmac_f32_e32 v108, v109, v113
	v_mul_f32_e32 v109, 0xbfb8aa3b, v104
	v_exp_f32_e32 v109, v109
	v_fma_f32 v102, -v112, v108, v102
	v_div_fmas_f32 v102, v102, v113, v108
	v_div_fixup_f32 v102, v102, v111, v103
	v_add_f32_e32 v109, 1.0, v109
	v_div_scale_f32 v110, s[42:43], v109, v109, v104
	v_rcp_f32_e32 v112, v110
	v_mul_f32_e32 v99, v102, v99
	v_mul_f32_e32 v102, 0xbfb8aa3b, v105
	v_exp_f32_e32 v102, v102
	v_cvt_pk_bf16_f32 v108, v98, v99
	v_fma_f32 v98, -v110, v112, 1.0
	v_fmac_f32_e32 v112, v98, v112
	v_div_scale_f32 v98, vcc, v104, v109, v104
	v_mul_f32_e32 v99, v98, v112
	v_fma_f32 v103, -v110, v99, v98
	v_add_f32_e32 v102, 1.0, v102
	v_fmac_f32_e32 v99, v103, v112
	v_div_scale_f32 v103, s[42:43], v102, v102, v105
	v_fma_f32 v98, -v110, v99, v98
	v_rcp_f32_e32 v110, v103
	v_div_fmas_f32 v98, v98, v112, v99
	v_div_fixup_f32 v98, v98, v109, v104
	v_mul_f32_e32 v98, v98, v100
	v_fma_f32 v99, -v103, v110, 1.0
	v_fmac_f32_e32 v110, v99, v110
	v_div_scale_f32 v99, vcc, v105, v102, v105
	v_mul_f32_e32 v100, v99, v110
	v_fma_f32 v104, -v103, v100, v99
	v_fmac_f32_e32 v100, v104, v110
	v_fma_f32 v99, -v103, v100, v99
	v_div_fmas_f32 v99, v99, v110, v100
	v_mul_f32_e32 v100, 0xbfb8aa3b, v94
	v_exp_f32_e32 v100, v100
	v_div_fixup_f32 v99, v99, v102, v105
	v_mul_f32_e32 v99, v99, v101
	v_cvt_pk_bf16_f32 v109, v98, v99
	v_add_f32_e32 v100, 1.0, v100
	v_div_scale_f32 v101, s[42:43], v100, v100, v94
	v_rcp_f32_e32 v102, v101
	v_or_b32_e32 v98, 16, v148
	v_mad_i64_i32 v[98:99], s[42:43], v98, s59, v[114:115]
	v_lshl_add_u64 v[98:99], v[98:99], 0, v[116:117]
	global_store_dwordx4 v[98:99], v[106:109], off
	v_fma_f32 v98, -v101, v102, 1.0
	v_mul_f32_e32 v103, 0xbfb8aa3b, v95
	v_fmac_f32_e32 v102, v98, v102
	v_div_scale_f32 v98, vcc, v94, v100, v94
	v_exp_f32_e32 v103, v103
	v_mul_f32_e32 v99, v98, v102
	v_fma_f32 v104, -v101, v99, v98
	v_fmac_f32_e32 v99, v104, v102
	v_fma_f32 v98, -v101, v99, v98
	v_add_f32_e32 v101, 1.0, v103
	v_div_scale_f32 v103, s[42:43], v101, v101, v95
	v_rcp_f32_e32 v104, v103
	v_div_fmas_f32 v98, v98, v102, v99
	v_div_fixup_f32 v94, v98, v100, v94
	v_mul_f32_e32 v90, v94, v90
	v_fma_f32 v94, -v103, v104, 1.0
	v_fmac_f32_e32 v104, v94, v104
	v_div_scale_f32 v94, vcc, v95, v101, v95
	v_mul_f32_e32 v98, v94, v104
	v_fma_f32 v99, -v103, v98, v94
	v_fmac_f32_e32 v98, v99, v104
	v_mul_f32_e32 v99, 0xbfb8aa3b, v96
	v_exp_f32_e32 v99, v99
	v_fma_f32 v94, -v103, v98, v94
	v_div_fmas_f32 v94, v94, v104, v98
	v_div_fixup_f32 v94, v94, v101, v95
	v_add_f32_e32 v98, 1.0, v99
	v_div_scale_f32 v99, s[42:43], v98, v98, v96
	v_rcp_f32_e32 v100, v99
	v_mul_f32_e32 v91, v94, v91
	v_mul_f32_e32 v95, 0xbfb8aa3b, v97
	v_cvt_pk_bf16_f32 v90, v90, v91
	v_fma_f32 v91, -v99, v100, 1.0
	v_exp_f32_e32 v95, v95
	v_fmac_f32_e32 v100, v91, v100
	v_div_scale_f32 v91, vcc, v96, v98, v96
	v_mul_f32_e32 v94, v91, v100
	v_fma_f32 v101, -v99, v94, v91
	v_fmac_f32_e32 v94, v101, v100
	v_add_f32_e32 v95, 1.0, v95
	v_fma_f32 v91, -v99, v94, v91
	v_div_scale_f32 v99, s[42:43], v95, v95, v97
	v_rcp_f32_e32 v101, v99
	v_div_fmas_f32 v91, v91, v100, v94
	v_div_fixup_f32 v91, v91, v98, v96
	v_mul_f32_e32 v91, v91, v92
	v_fma_f32 v92, -v99, v101, 1.0
	v_fmac_f32_e32 v101, v92, v101
	v_div_scale_f32 v92, vcc, v97, v95, v97
	v_mul_f32_e32 v94, v92, v101
	v_fma_f32 v96, -v99, v94, v92
	v_fmac_f32_e32 v94, v96, v101
	v_mul_f32_e32 v96, 0xbfb8aa3b, v86
	v_exp_f32_e32 v96, v96
	v_fma_f32 v92, -v99, v94, v92
	v_div_fmas_f32 v92, v92, v101, v94
	v_div_fixup_f32 v92, v92, v95, v97
	v_add_f32_e32 v94, 1.0, v96
	v_div_scale_f32 v96, s[42:43], v94, v94, v86
	v_rcp_f32_e32 v98, v96
	v_mul_f32_e32 v92, v92, v93
	v_mul_f32_e32 v95, 0xbfb8aa3b, v87
	v_cvt_pk_bf16_f32 v91, v91, v92
	v_fma_f32 v92, -v96, v98, 1.0
	v_exp_f32_e32 v95, v95
	v_fmac_f32_e32 v98, v92, v98
	v_div_scale_f32 v92, vcc, v86, v94, v86
	v_mul_f32_e32 v93, v92, v98
	v_fma_f32 v97, -v96, v93, v92
	v_fmac_f32_e32 v93, v97, v98
	v_add_f32_e32 v95, 1.0, v95
	v_fma_f32 v92, -v96, v93, v92
	v_div_scale_f32 v96, s[42:43], v95, v95, v87
	v_rcp_f32_e32 v97, v96
	v_div_fmas_f32 v92, v92, v98, v93
	v_div_fixup_f32 v86, v92, v94, v86
	v_mul_f32_e32 v82, v86, v82
	v_fma_f32 v86, -v96, v97, 1.0
	v_fmac_f32_e32 v97, v86, v97
	v_div_scale_f32 v86, vcc, v87, v95, v87
	v_mul_f32_e32 v92, v86, v97
	v_fma_f32 v93, -v96, v92, v86
	v_fmac_f32_e32 v92, v93, v97
	v_mul_f32_e32 v93, 0xbfb8aa3b, v88
	v_exp_f32_e32 v93, v93
	v_fma_f32 v86, -v96, v92, v86
	v_div_fmas_f32 v86, v86, v97, v92
	v_div_fixup_f32 v86, v86, v95, v87
	v_add_f32_e32 v93, 1.0, v93
	v_div_scale_f32 v94, s[42:43], v93, v93, v88
	v_rcp_f32_e32 v96, v94
	v_mul_f32_e32 v83, v86, v83
	v_mul_f32_e32 v86, 0xbfb8aa3b, v89
	v_exp_f32_e32 v86, v86
	v_cvt_pk_bf16_f32 v92, v82, v83
	v_fma_f32 v82, -v94, v96, 1.0
	v_fmac_f32_e32 v96, v82, v96
	v_div_scale_f32 v82, vcc, v88, v93, v88
	v_mul_f32_e32 v83, v82, v96
	v_fma_f32 v87, -v94, v83, v82
	v_add_f32_e32 v86, 1.0, v86
	v_fmac_f32_e32 v83, v87, v96
	v_div_scale_f32 v87, s[42:43], v86, v86, v89
	v_fma_f32 v82, -v94, v83, v82
	v_rcp_f32_e32 v94, v87
	v_div_fmas_f32 v82, v82, v96, v83
	v_div_fixup_f32 v82, v82, v93, v88
	v_mul_f32_e32 v82, v82, v84
	v_fma_f32 v83, -v87, v94, 1.0
	v_fmac_f32_e32 v94, v83, v94
	v_div_scale_f32 v83, vcc, v89, v86, v89
	v_mul_f32_e32 v84, v83, v94
	v_fma_f32 v88, -v87, v84, v83
	v_fmac_f32_e32 v84, v88, v94
	v_fma_f32 v83, -v87, v84, v83
	v_div_fmas_f32 v83, v83, v94, v84
	v_mul_f32_e32 v84, 0xbfb8aa3b, v78
	v_exp_f32_e32 v84, v84
	v_div_fixup_f32 v83, v83, v86, v89
	v_mul_f32_e32 v83, v83, v85
	v_cvt_pk_bf16_f32 v93, v82, v83
	v_add_f32_e32 v84, 1.0, v84
	v_div_scale_f32 v85, s[42:43], v84, v84, v78
	v_rcp_f32_e32 v86, v85
	v_or_b32_e32 v82, 32, v148
	v_mad_i64_i32 v[82:83], s[42:43], v82, s59, v[114:115]
	v_lshl_add_u64 v[82:83], v[82:83], 0, v[116:117]
	global_store_dwordx4 v[82:83], v[90:93], off
	v_fma_f32 v82, -v85, v86, 1.0
	v_mul_f32_e32 v87, 0xbfb8aa3b, v79
	v_fmac_f32_e32 v86, v82, v86
	v_div_scale_f32 v82, vcc, v78, v84, v78
	v_exp_f32_e32 v87, v87
	v_mul_f32_e32 v83, v82, v86
	v_fma_f32 v88, -v85, v83, v82
	v_fmac_f32_e32 v83, v88, v86
	v_fma_f32 v82, -v85, v83, v82
	v_add_f32_e32 v85, 1.0, v87
	v_div_scale_f32 v87, s[42:43], v85, v85, v79
	v_rcp_f32_e32 v88, v87
	v_div_fmas_f32 v82, v82, v86, v83
	v_div_fixup_f32 v78, v82, v84, v78
	v_mul_f32_e32 v74, v78, v74
	v_fma_f32 v78, -v87, v88, 1.0
	v_fmac_f32_e32 v88, v78, v88
	v_div_scale_f32 v78, vcc, v79, v85, v79
	v_mul_f32_e32 v82, v78, v88
	v_fma_f32 v83, -v87, v82, v78
	v_fmac_f32_e32 v82, v83, v88
	v_mul_f32_e32 v83, 0xbfb8aa3b, v80
	v_exp_f32_e32 v83, v83
	v_fma_f32 v78, -v87, v82, v78
	v_div_fmas_f32 v78, v78, v88, v82
	v_div_fixup_f32 v78, v78, v85, v79
	v_add_f32_e32 v82, 1.0, v83
	v_div_scale_f32 v83, s[42:43], v82, v82, v80
	v_rcp_f32_e32 v84, v83
	v_mul_f32_e32 v75, v78, v75
	v_mul_f32_e32 v79, 0xbfb8aa3b, v81
	v_cvt_pk_bf16_f32 v74, v74, v75
	v_fma_f32 v75, -v83, v84, 1.0
	v_exp_f32_e32 v79, v79
	v_fmac_f32_e32 v84, v75, v84
	v_div_scale_f32 v75, vcc, v80, v82, v80
	v_mul_f32_e32 v78, v75, v84
	v_fma_f32 v85, -v83, v78, v75
	v_fmac_f32_e32 v78, v85, v84
	v_add_f32_e32 v79, 1.0, v79
	v_fma_f32 v75, -v83, v78, v75
	v_div_scale_f32 v83, s[42:43], v79, v79, v81
	v_rcp_f32_e32 v85, v83
	v_div_fmas_f32 v75, v75, v84, v78
	v_div_fixup_f32 v75, v75, v82, v80
	v_mul_f32_e32 v75, v75, v76
	v_fma_f32 v76, -v83, v85, 1.0
	v_fmac_f32_e32 v85, v76, v85
	v_div_scale_f32 v76, vcc, v81, v79, v81
	v_mul_f32_e32 v78, v76, v85
	v_fma_f32 v80, -v83, v78, v76
	v_fmac_f32_e32 v78, v80, v85
	v_mul_f32_e32 v80, 0xbfb8aa3b, v70
	v_exp_f32_e32 v80, v80
	v_fma_f32 v76, -v83, v78, v76
	v_div_fmas_f32 v76, v76, v85, v78
	v_div_fixup_f32 v76, v76, v79, v81
	v_add_f32_e32 v78, 1.0, v80
	v_div_scale_f32 v80, s[42:43], v78, v78, v70
	v_rcp_f32_e32 v82, v80
	v_mul_f32_e32 v76, v76, v77
	v_mul_f32_e32 v79, 0xbfb8aa3b, v71
	v_cvt_pk_bf16_f32 v75, v75, v76
	v_fma_f32 v76, -v80, v82, 1.0
	v_exp_f32_e32 v79, v79
	v_fmac_f32_e32 v82, v76, v82
	v_div_scale_f32 v76, vcc, v70, v78, v70
	v_mul_f32_e32 v77, v76, v82
	v_fma_f32 v81, -v80, v77, v76
	v_fmac_f32_e32 v77, v81, v82
	v_add_f32_e32 v79, 1.0, v79
	v_fma_f32 v76, -v80, v77, v76
	v_div_scale_f32 v80, s[42:43], v79, v79, v71
	v_rcp_f32_e32 v81, v80
	v_div_fmas_f32 v76, v76, v82, v77
	v_div_fixup_f32 v70, v76, v78, v70
	v_mul_f32_e32 v66, v70, v66
	v_fma_f32 v70, -v80, v81, 1.0
	v_fmac_f32_e32 v81, v70, v81
	v_div_scale_f32 v70, vcc, v71, v79, v71
	v_mul_f32_e32 v76, v70, v81
	v_fma_f32 v77, -v80, v76, v70
	v_fmac_f32_e32 v76, v77, v81
	v_mul_f32_e32 v77, 0xbfb8aa3b, v72
	v_exp_f32_e32 v77, v77
	v_fma_f32 v70, -v80, v76, v70
	v_div_fmas_f32 v70, v70, v81, v76
	v_div_fixup_f32 v70, v70, v79, v71
	v_add_f32_e32 v77, 1.0, v77
	v_div_scale_f32 v78, s[42:43], v77, v77, v72
	v_rcp_f32_e32 v80, v78
	v_mul_f32_e32 v67, v70, v67
	v_mul_f32_e32 v70, 0xbfb8aa3b, v73
	v_exp_f32_e32 v70, v70
	v_cvt_pk_bf16_f32 v76, v66, v67
	v_fma_f32 v66, -v78, v80, 1.0
	v_fmac_f32_e32 v80, v66, v80
	v_div_scale_f32 v66, vcc, v72, v77, v72
	v_mul_f32_e32 v67, v66, v80
	v_fma_f32 v71, -v78, v67, v66
	v_add_f32_e32 v70, 1.0, v70
	v_fmac_f32_e32 v67, v71, v80
	v_div_scale_f32 v71, s[42:43], v70, v70, v73
	v_fma_f32 v66, -v78, v67, v66
	v_rcp_f32_e32 v78, v71
	v_div_fmas_f32 v66, v66, v80, v67
	v_div_fixup_f32 v66, v66, v77, v72
	v_mul_f32_e32 v66, v66, v68
	v_fma_f32 v67, -v71, v78, 1.0
	v_fmac_f32_e32 v78, v67, v78
	v_div_scale_f32 v67, vcc, v73, v70, v73
	v_mul_f32_e32 v68, v67, v78
	v_fma_f32 v72, -v71, v68, v67
	v_fmac_f32_e32 v68, v72, v78
	v_fma_f32 v67, -v71, v68, v67
	v_div_fmas_f32 v67, v67, v78, v68
	v_div_fixup_f32 v67, v67, v70, v73
	v_mul_f32_e32 v67, v67, v69
	v_cvt_pk_bf16_f32 v77, v66, v67
	v_mul_f32_e32 v66, 0xbfb8aa3b, v62
	v_exp_f32_e32 v68, v66
	v_or_b32_e32 v66, 48, v148
	v_mad_i64_i32 v[66:67], s[42:43], v66, s59, v[114:115]
	v_add_f32_e32 v68, 1.0, v68
	v_div_scale_f32 v69, s[42:43], v68, v68, v62
	v_rcp_f32_e32 v70, v69
	v_lshl_add_u64 v[66:67], v[66:67], 0, v[116:117]
	global_store_dwordx4 v[66:67], v[74:77], off
	v_mul_f32_e32 v72, 0xbfb8aa3b, v63
	v_fma_f32 v67, -v69, v70, 1.0
	v_fmac_f32_e32 v70, v67, v70
	v_div_scale_f32 v67, vcc, v62, v68, v62
	v_exp_f32_e32 v72, v72
	v_mul_f32_e32 v71, v67, v70
	v_fma_f32 v73, -v69, v71, v67
	v_fmac_f32_e32 v71, v73, v70
	v_fma_f32 v67, -v69, v71, v67
	v_add_f32_e32 v69, 1.0, v72
	v_div_scale_f32 v72, s[42:43], v69, v69, v63
	v_rcp_f32_e32 v73, v72
	v_div_fmas_f32 v67, v67, v70, v71
	v_div_fixup_f32 v62, v67, v68, v62
	v_mul_f32_e32 v58, v62, v58
	v_fma_f32 v62, -v72, v73, 1.0
	v_fmac_f32_e32 v73, v62, v73
	v_div_scale_f32 v62, vcc, v63, v69, v63
	v_mul_f32_e32 v67, v62, v73
	v_fma_f32 v68, -v72, v67, v62
	v_fmac_f32_e32 v67, v68, v73
	v_mul_f32_e32 v68, 0xbfb8aa3b, v64
	v_exp_f32_e32 v68, v68
	v_fma_f32 v62, -v72, v67, v62
	v_div_fmas_f32 v62, v62, v73, v67
	v_div_fixup_f32 v62, v62, v69, v63
	v_add_f32_e32 v67, 1.0, v68
	v_div_scale_f32 v68, s[42:43], v67, v67, v64
	v_rcp_f32_e32 v70, v68
	v_mul_f32_e32 v59, v62, v59
	v_mul_f32_e32 v63, 0xbfb8aa3b, v65
	v_cvt_pk_bf16_f32 v58, v58, v59
	v_fma_f32 v59, -v68, v70, 1.0
	v_exp_f32_e32 v63, v63
	v_fmac_f32_e32 v70, v59, v70
	v_div_scale_f32 v59, vcc, v64, v67, v64
	v_mul_f32_e32 v62, v59, v70
	v_fma_f32 v69, -v68, v62, v59
	v_fmac_f32_e32 v62, v69, v70
	v_add_f32_e32 v63, 1.0, v63
	v_fma_f32 v59, -v68, v62, v59
	v_div_scale_f32 v68, s[42:43], v63, v63, v65
	v_rcp_f32_e32 v69, v68
	v_div_fmas_f32 v59, v59, v70, v62
	v_div_fixup_f32 v59, v59, v67, v64
	v_mul_f32_e32 v59, v59, v60
	v_fma_f32 v60, -v68, v69, 1.0
	v_fmac_f32_e32 v69, v60, v69
	v_div_scale_f32 v60, vcc, v65, v63, v65
	v_mul_f32_e32 v62, v60, v69
	v_fma_f32 v64, -v68, v62, v60
	v_fmac_f32_e32 v62, v64, v69
	v_mul_f32_e32 v64, 0xbfb8aa3b, v54
	v_exp_f32_e32 v64, v64
	v_fma_f32 v60, -v68, v62, v60
	v_div_fmas_f32 v60, v60, v69, v62
	v_div_fixup_f32 v60, v60, v63, v65
	v_add_f32_e32 v62, 1.0, v64
	v_div_scale_f32 v64, s[42:43], v62, v62, v54
	v_rcp_f32_e32 v67, v64
	v_mul_f32_e32 v60, v60, v61
	v_mul_f32_e32 v63, 0xbfb8aa3b, v55
	v_cvt_pk_bf16_f32 v59, v59, v60
	v_fma_f32 v60, -v64, v67, 1.0
	v_exp_f32_e32 v63, v63
	v_fmac_f32_e32 v67, v60, v67
	v_div_scale_f32 v60, vcc, v54, v62, v54
	v_mul_f32_e32 v61, v60, v67
	v_fma_f32 v65, -v64, v61, v60
	v_fmac_f32_e32 v61, v65, v67
	v_add_f32_e32 v63, 1.0, v63
	v_fma_f32 v60, -v64, v61, v60
	v_div_scale_f32 v64, s[42:43], v63, v63, v55
	v_rcp_f32_e32 v65, v64
	v_div_fmas_f32 v60, v60, v67, v61
	v_div_fixup_f32 v54, v60, v62, v54
	v_mul_f32_e32 v50, v54, v50
	v_fma_f32 v54, -v64, v65, 1.0
	v_fmac_f32_e32 v65, v54, v65
	v_div_scale_f32 v54, vcc, v55, v63, v55
	v_mul_f32_e32 v60, v54, v65
	v_fma_f32 v61, -v64, v60, v54
	v_fmac_f32_e32 v60, v61, v65
	v_mul_f32_e32 v61, 0xbfb8aa3b, v56
	v_exp_f32_e32 v61, v61
	v_fma_f32 v54, -v64, v60, v54
	v_div_fmas_f32 v54, v54, v65, v60
	v_div_fixup_f32 v54, v54, v63, v55
	v_add_f32_e32 v61, 1.0, v61
	v_div_scale_f32 v62, s[42:43], v61, v61, v56
	v_rcp_f32_e32 v64, v62
	v_mul_f32_e32 v51, v54, v51
	v_mul_f32_e32 v54, 0xbfb8aa3b, v57
	v_exp_f32_e32 v54, v54
	v_cvt_pk_bf16_f32 v60, v50, v51
	v_fma_f32 v50, -v62, v64, 1.0
	v_fmac_f32_e32 v64, v50, v64
	v_div_scale_f32 v50, vcc, v56, v61, v56
	v_mul_f32_e32 v51, v50, v64
	v_fma_f32 v55, -v62, v51, v50
	v_add_f32_e32 v54, 1.0, v54
	v_fmac_f32_e32 v51, v55, v64
	v_div_scale_f32 v55, s[42:43], v54, v54, v57
	v_fma_f32 v50, -v62, v51, v50
	v_rcp_f32_e32 v62, v55
	v_div_fmas_f32 v50, v50, v64, v51
	v_div_fixup_f32 v50, v50, v61, v56
	v_mul_f32_e32 v50, v50, v52
	v_fma_f32 v51, -v55, v62, 1.0
	v_fmac_f32_e32 v62, v51, v62
	v_div_scale_f32 v51, vcc, v57, v54, v57
	v_mul_f32_e32 v52, v51, v62
	v_fma_f32 v56, -v55, v52, v51
	v_fmac_f32_e32 v52, v56, v62
	v_fma_f32 v51, -v55, v52, v51
	v_div_fmas_f32 v51, v51, v62, v52
	v_mul_f32_e32 v52, 0xbfb8aa3b, v46
	v_exp_f32_e32 v52, v52
	v_div_fixup_f32 v51, v51, v54, v57
	v_mul_f32_e32 v51, v51, v53
	v_add_u32_e32 v66, 0x80, v148
	v_add_f32_e32 v52, 1.0, v52
	v_div_scale_f32 v53, s[42:43], v52, v52, v46
	v_rcp_f32_e32 v54, v53
	v_cvt_pk_bf16_f32 v61, v50, v51
	v_mad_i64_i32 v[50:51], s[42:43], v66, s59, v[114:115]
	v_lshl_add_u64 v[50:51], v[50:51], 0, v[116:117]
	global_store_dwordx4 v[50:51], v[58:61], off
	v_fma_f32 v50, -v53, v54, 1.0
	v_mul_f32_e32 v55, 0xbfb8aa3b, v47
	v_fmac_f32_e32 v54, v50, v54
	v_div_scale_f32 v50, vcc, v46, v52, v46
	v_exp_f32_e32 v55, v55
	v_mul_f32_e32 v51, v50, v54
	v_fma_f32 v56, -v53, v51, v50
	v_fmac_f32_e32 v51, v56, v54
	v_fma_f32 v50, -v53, v51, v50
	v_add_f32_e32 v53, 1.0, v55
	v_div_scale_f32 v55, s[42:43], v53, v53, v47
	v_rcp_f32_e32 v56, v55
	v_div_fmas_f32 v50, v50, v54, v51
	v_div_fixup_f32 v46, v50, v52, v46
	v_mul_f32_e32 v42, v46, v42
	v_fma_f32 v46, -v55, v56, 1.0
	v_fmac_f32_e32 v56, v46, v56
	v_div_scale_f32 v46, vcc, v47, v53, v47
	v_mul_f32_e32 v50, v46, v56
	v_fma_f32 v51, -v55, v50, v46
	v_fmac_f32_e32 v50, v51, v56
	v_mul_f32_e32 v51, 0xbfb8aa3b, v48
	v_exp_f32_e32 v51, v51
	v_fma_f32 v46, -v55, v50, v46
	v_div_fmas_f32 v46, v46, v56, v50
	v_div_fixup_f32 v46, v46, v53, v47
	v_add_f32_e32 v50, 1.0, v51
	v_div_scale_f32 v51, s[42:43], v50, v50, v48
	v_rcp_f32_e32 v52, v51
	v_mul_f32_e32 v43, v46, v43
	v_mul_f32_e32 v47, 0xbfb8aa3b, v49
	v_cvt_pk_bf16_f32 v42, v42, v43
	v_fma_f32 v43, -v51, v52, 1.0
	v_exp_f32_e32 v47, v47
	v_fmac_f32_e32 v52, v43, v52
	v_div_scale_f32 v43, vcc, v48, v50, v48
	v_mul_f32_e32 v46, v43, v52
	v_fma_f32 v53, -v51, v46, v43
	v_fmac_f32_e32 v46, v53, v52
	v_add_f32_e32 v47, 1.0, v47
	v_fma_f32 v43, -v51, v46, v43
	v_div_scale_f32 v51, s[42:43], v47, v47, v49
	v_rcp_f32_e32 v53, v51
	v_div_fmas_f32 v43, v43, v52, v46
	v_div_fixup_f32 v43, v43, v50, v48
	v_mul_f32_e32 v43, v43, v44
	v_fma_f32 v44, -v51, v53, 1.0
	v_fmac_f32_e32 v53, v44, v53
	v_div_scale_f32 v44, vcc, v49, v47, v49
	v_mul_f32_e32 v46, v44, v53
	v_fma_f32 v48, -v51, v46, v44
	v_fmac_f32_e32 v46, v48, v53
	v_mul_f32_e32 v48, 0xbfb8aa3b, v38
	v_exp_f32_e32 v48, v48
	v_fma_f32 v44, -v51, v46, v44
	v_div_fmas_f32 v44, v44, v53, v46
	v_div_fixup_f32 v44, v44, v47, v49
	v_add_f32_e32 v46, 1.0, v48
	v_div_scale_f32 v48, s[42:43], v46, v46, v38
	v_rcp_f32_e32 v50, v48
	v_mul_f32_e32 v44, v44, v45
	v_mul_f32_e32 v47, 0xbfb8aa3b, v39
	v_cvt_pk_bf16_f32 v43, v43, v44
	v_fma_f32 v44, -v48, v50, 1.0
	v_exp_f32_e32 v47, v47
	v_fmac_f32_e32 v50, v44, v50
	v_div_scale_f32 v44, vcc, v38, v46, v38
	v_mul_f32_e32 v45, v44, v50
	v_fma_f32 v49, -v48, v45, v44
	v_fmac_f32_e32 v45, v49, v50
	v_add_f32_e32 v47, 1.0, v47
	v_fma_f32 v44, -v48, v45, v44
	v_div_scale_f32 v48, s[42:43], v47, v47, v39
	v_rcp_f32_e32 v49, v48
	v_div_fmas_f32 v44, v44, v50, v45
	v_div_fixup_f32 v38, v44, v46, v38
	v_mul_f32_e32 v34, v38, v34
	v_fma_f32 v38, -v48, v49, 1.0
	v_fmac_f32_e32 v49, v38, v49
	v_div_scale_f32 v38, vcc, v39, v47, v39
	v_mul_f32_e32 v44, v38, v49
	v_fma_f32 v45, -v48, v44, v38
	v_fmac_f32_e32 v44, v45, v49
	v_mul_f32_e32 v45, 0xbfb8aa3b, v40
	v_exp_f32_e32 v45, v45
	v_fma_f32 v38, -v48, v44, v38
	v_div_fmas_f32 v38, v38, v49, v44
	v_div_fixup_f32 v38, v38, v47, v39
	v_add_f32_e32 v45, 1.0, v45
	v_div_scale_f32 v46, s[42:43], v45, v45, v40
	v_rcp_f32_e32 v48, v46
	v_mul_f32_e32 v35, v38, v35
	v_mul_f32_e32 v38, 0xbfb8aa3b, v41
	v_exp_f32_e32 v38, v38
	v_cvt_pk_bf16_f32 v44, v34, v35
	v_fma_f32 v34, -v46, v48, 1.0
	v_fmac_f32_e32 v48, v34, v48
	v_div_scale_f32 v34, vcc, v40, v45, v40
	v_mul_f32_e32 v35, v34, v48
	v_fma_f32 v39, -v46, v35, v34
	v_add_f32_e32 v38, 1.0, v38
	v_fmac_f32_e32 v35, v39, v48
	v_div_scale_f32 v39, s[42:43], v38, v38, v41
	v_fma_f32 v34, -v46, v35, v34
	v_rcp_f32_e32 v46, v39
	v_div_fmas_f32 v34, v34, v48, v35
	v_div_fixup_f32 v34, v34, v45, v40
	v_mul_f32_e32 v34, v34, v36
	v_fma_f32 v35, -v39, v46, 1.0
	v_fmac_f32_e32 v46, v35, v46
	v_div_scale_f32 v35, vcc, v41, v38, v41
	v_mul_f32_e32 v36, v35, v46
	v_fma_f32 v40, -v39, v36, v35
	v_fmac_f32_e32 v36, v40, v46
	v_fma_f32 v35, -v39, v36, v35
	v_div_fmas_f32 v35, v35, v46, v36
	v_mul_f32_e32 v36, 0xbfb8aa3b, v30
	v_exp_f32_e32 v36, v36
	v_div_fixup_f32 v35, v35, v38, v41
	v_mul_f32_e32 v35, v35, v37
	v_cvt_pk_bf16_f32 v45, v34, v35
	v_add_f32_e32 v36, 1.0, v36
	v_div_scale_f32 v37, s[42:43], v36, v36, v30
	v_rcp_f32_e32 v38, v37
	v_add_u32_e32 v34, 0x90, v148
	v_mad_i64_i32 v[34:35], s[42:43], v34, s59, v[114:115]
	v_lshl_add_u64 v[34:35], v[34:35], 0, v[116:117]
	global_store_dwordx4 v[34:35], v[42:45], off
	v_fma_f32 v34, -v37, v38, 1.0
	v_mul_f32_e32 v39, 0xbfb8aa3b, v31
	v_fmac_f32_e32 v38, v34, v38
	v_div_scale_f32 v34, vcc, v30, v36, v30
	v_exp_f32_e32 v39, v39
	v_mul_f32_e32 v35, v34, v38
	v_fma_f32 v40, -v37, v35, v34
	v_fmac_f32_e32 v35, v40, v38
	v_fma_f32 v34, -v37, v35, v34
	v_add_f32_e32 v37, 1.0, v39
	v_div_scale_f32 v39, s[42:43], v37, v37, v31
	v_rcp_f32_e32 v40, v39
	v_div_fmas_f32 v34, v34, v38, v35
	v_div_fixup_f32 v30, v34, v36, v30
	v_mul_f32_e32 v26, v30, v26
	v_fma_f32 v30, -v39, v40, 1.0
	v_fmac_f32_e32 v40, v30, v40
	v_div_scale_f32 v30, vcc, v31, v37, v31
	v_mul_f32_e32 v34, v30, v40
	v_fma_f32 v35, -v39, v34, v30
	v_fmac_f32_e32 v34, v35, v40
	v_mul_f32_e32 v35, 0xbfb8aa3b, v32
	v_exp_f32_e32 v35, v35
	v_fma_f32 v30, -v39, v34, v30
	v_div_fmas_f32 v30, v30, v40, v34
	v_div_fixup_f32 v30, v30, v37, v31
	v_add_f32_e32 v34, 1.0, v35
	v_div_scale_f32 v35, s[42:43], v34, v34, v32
	v_rcp_f32_e32 v36, v35
	v_mul_f32_e32 v27, v30, v27
	v_mul_f32_e32 v31, 0xbfb8aa3b, v33
	v_cvt_pk_bf16_f32 v26, v26, v27
	v_fma_f32 v27, -v35, v36, 1.0
	v_exp_f32_e32 v31, v31
	v_fmac_f32_e32 v36, v27, v36
	v_div_scale_f32 v27, vcc, v32, v34, v32
	v_mul_f32_e32 v30, v27, v36
	v_fma_f32 v37, -v35, v30, v27
	v_fmac_f32_e32 v30, v37, v36
	v_add_f32_e32 v31, 1.0, v31
	v_fma_f32 v27, -v35, v30, v27
	v_div_scale_f32 v35, s[42:43], v31, v31, v33
	v_rcp_f32_e32 v37, v35
	v_div_fmas_f32 v27, v27, v36, v30
	v_div_fixup_f32 v27, v27, v34, v32
	v_mul_f32_e32 v27, v27, v28
	v_fma_f32 v28, -v35, v37, 1.0
	v_fmac_f32_e32 v37, v28, v37
	v_div_scale_f32 v28, vcc, v33, v31, v33
	v_mul_f32_e32 v30, v28, v37
	v_fma_f32 v32, -v35, v30, v28
	v_fmac_f32_e32 v30, v32, v37
	v_mul_f32_e32 v32, 0xbfb8aa3b, v22
	v_exp_f32_e32 v32, v32
	v_fma_f32 v28, -v35, v30, v28
	v_div_fmas_f32 v28, v28, v37, v30
	v_div_fixup_f32 v28, v28, v31, v33
	v_add_f32_e32 v30, 1.0, v32
	v_div_scale_f32 v32, s[42:43], v30, v30, v22
	v_rcp_f32_e32 v34, v32
	v_mul_f32_e32 v28, v28, v29
	v_mul_f32_e32 v31, 0xbfb8aa3b, v23
	v_cvt_pk_bf16_f32 v27, v27, v28
	v_fma_f32 v28, -v32, v34, 1.0
	v_exp_f32_e32 v31, v31
	v_fmac_f32_e32 v34, v28, v34
	v_div_scale_f32 v28, vcc, v22, v30, v22
	v_mul_f32_e32 v29, v28, v34
	v_fma_f32 v33, -v32, v29, v28
	v_fmac_f32_e32 v29, v33, v34
	v_add_f32_e32 v31, 1.0, v31
	v_fma_f32 v28, -v32, v29, v28
	v_div_scale_f32 v32, s[42:43], v31, v31, v23
	v_rcp_f32_e32 v33, v32
	v_div_fmas_f32 v28, v28, v34, v29
	v_div_fixup_f32 v22, v28, v30, v22
	v_mul_f32_e32 v18, v22, v18
	v_fma_f32 v22, -v32, v33, 1.0
	v_fmac_f32_e32 v33, v22, v33
	v_div_scale_f32 v22, vcc, v23, v31, v23
	v_mul_f32_e32 v28, v22, v33
	v_fma_f32 v29, -v32, v28, v22
	v_fmac_f32_e32 v28, v29, v33
	v_mul_f32_e32 v29, 0xbfb8aa3b, v24
	v_exp_f32_e32 v29, v29
	v_fma_f32 v22, -v32, v28, v22
	v_div_fmas_f32 v22, v22, v33, v28
	v_div_fixup_f32 v22, v22, v31, v23
	v_add_f32_e32 v29, 1.0, v29
	v_div_scale_f32 v30, s[42:43], v29, v29, v24
	v_rcp_f32_e32 v32, v30
	v_mul_f32_e32 v19, v22, v19
	v_mul_f32_e32 v22, 0xbfb8aa3b, v25
	v_exp_f32_e32 v22, v22
	v_cvt_pk_bf16_f32 v28, v18, v19
	v_fma_f32 v18, -v30, v32, 1.0
	v_fmac_f32_e32 v32, v18, v32
	v_div_scale_f32 v18, vcc, v24, v29, v24
	v_mul_f32_e32 v19, v18, v32
	v_fma_f32 v23, -v30, v19, v18
	v_add_f32_e32 v22, 1.0, v22
	v_fmac_f32_e32 v19, v23, v32
	v_div_scale_f32 v23, s[42:43], v22, v22, v25
	v_fma_f32 v18, -v30, v19, v18
	v_rcp_f32_e32 v30, v23
	v_div_fmas_f32 v18, v18, v32, v19
	v_div_fixup_f32 v18, v18, v29, v24
	v_mul_f32_e32 v18, v18, v20
	v_fma_f32 v19, -v23, v30, 1.0
	v_fmac_f32_e32 v30, v19, v30
	v_div_scale_f32 v19, vcc, v25, v22, v25
	v_mul_f32_e32 v20, v19, v30
	v_fma_f32 v24, -v23, v20, v19
	v_fmac_f32_e32 v20, v24, v30
	v_fma_f32 v19, -v23, v20, v19
	v_div_fmas_f32 v19, v19, v30, v20
	v_mul_f32_e32 v20, 0xbfb8aa3b, v14
	v_exp_f32_e32 v20, v20
	v_div_fixup_f32 v19, v19, v22, v25
	v_mul_f32_e32 v19, v19, v21
	v_cvt_pk_bf16_f32 v29, v18, v19
	v_add_f32_e32 v20, 1.0, v20
	v_div_scale_f32 v21, s[42:43], v20, v20, v14
	v_rcp_f32_e32 v22, v21
	v_add_u32_e32 v18, 0xa0, v148
	v_mad_i64_i32 v[18:19], s[42:43], v18, s59, v[114:115]
	v_lshl_add_u64 v[18:19], v[18:19], 0, v[116:117]
	global_store_dwordx4 v[18:19], v[26:29], off
	v_fma_f32 v18, -v21, v22, 1.0
	v_mul_f32_e32 v23, 0xbfb8aa3b, v15
	v_fmac_f32_e32 v22, v18, v22
	v_div_scale_f32 v18, vcc, v14, v20, v14
	v_exp_f32_e32 v23, v23
	v_mul_f32_e32 v19, v18, v22
	v_fma_f32 v24, -v21, v19, v18
	v_fmac_f32_e32 v19, v24, v22
	v_fma_f32 v18, -v21, v19, v18
	v_add_f32_e32 v21, 1.0, v23
	v_div_scale_f32 v23, s[42:43], v21, v21, v15
	v_rcp_f32_e32 v24, v23
	v_div_fmas_f32 v18, v18, v22, v19
	v_div_fixup_f32 v14, v18, v20, v14
	v_mul_f32_e32 v10, v14, v10
	v_fma_f32 v14, -v23, v24, 1.0
	v_fmac_f32_e32 v24, v14, v24
	v_div_scale_f32 v14, vcc, v15, v21, v15
	v_mul_f32_e32 v18, v14, v24
	v_fma_f32 v19, -v23, v18, v14
	v_fmac_f32_e32 v18, v19, v24
	v_mul_f32_e32 v19, 0xbfb8aa3b, v16
	v_exp_f32_e32 v19, v19
	v_fma_f32 v14, -v23, v18, v14
	v_div_fmas_f32 v14, v14, v24, v18
	v_div_fixup_f32 v14, v14, v21, v15
	v_add_f32_e32 v18, 1.0, v19
	v_div_scale_f32 v19, s[42:43], v18, v18, v16
	v_rcp_f32_e32 v20, v19
	v_mul_f32_e32 v11, v14, v11
	v_mul_f32_e32 v15, 0xbfb8aa3b, v17
	v_cvt_pk_bf16_f32 v10, v10, v11
	v_fma_f32 v11, -v19, v20, 1.0
	v_exp_f32_e32 v15, v15
	v_fmac_f32_e32 v20, v11, v20
	v_div_scale_f32 v11, vcc, v16, v18, v16
	v_mul_f32_e32 v14, v11, v20
	v_fma_f32 v21, -v19, v14, v11
	v_fmac_f32_e32 v14, v21, v20
	v_add_f32_e32 v15, 1.0, v15
	v_fma_f32 v11, -v19, v14, v11
	v_div_scale_f32 v19, s[42:43], v15, v15, v17
	v_rcp_f32_e32 v21, v19
	v_div_fmas_f32 v11, v11, v20, v14
	v_div_fixup_f32 v11, v11, v18, v16
	v_mul_f32_e32 v11, v11, v12
	v_fma_f32 v12, -v19, v21, 1.0
	v_fmac_f32_e32 v21, v12, v21
	v_div_scale_f32 v12, vcc, v17, v15, v17
	v_mul_f32_e32 v14, v12, v21
	v_fma_f32 v16, -v19, v14, v12
	v_fmac_f32_e32 v14, v16, v21
	v_mul_f32_e32 v16, 0xbfb8aa3b, v6
	v_exp_f32_e32 v16, v16
	v_fma_f32 v12, -v19, v14, v12
	v_div_fmas_f32 v12, v12, v21, v14
	v_div_fixup_f32 v12, v12, v15, v17
	v_add_f32_e32 v14, 1.0, v16
	v_div_scale_f32 v16, s[42:43], v14, v14, v6
	v_rcp_f32_e32 v18, v16
	v_mul_f32_e32 v12, v12, v13
	v_mul_f32_e32 v15, 0xbfb8aa3b, v7
	v_cvt_pk_bf16_f32 v11, v11, v12
	v_fma_f32 v12, -v16, v18, 1.0
	v_exp_f32_e32 v15, v15
	v_fmac_f32_e32 v18, v12, v18
	v_div_scale_f32 v12, vcc, v6, v14, v6
	v_mul_f32_e32 v13, v12, v18
	v_fma_f32 v17, -v16, v13, v12
	v_fmac_f32_e32 v13, v17, v18
	v_add_f32_e32 v15, 1.0, v15
	v_fma_f32 v12, -v16, v13, v12
	v_div_scale_f32 v16, s[42:43], v15, v15, v7
	v_rcp_f32_e32 v17, v16
	v_div_fmas_f32 v12, v12, v18, v13
	v_div_fixup_f32 v6, v12, v14, v6
	v_mul_f32_e32 v2, v6, v2
	v_fma_f32 v6, -v16, v17, 1.0
	v_fmac_f32_e32 v17, v6, v17
	v_div_scale_f32 v6, vcc, v7, v15, v7
	v_mul_f32_e32 v12, v6, v17
	v_fma_f32 v13, -v16, v12, v6
	v_fmac_f32_e32 v12, v13, v17
	v_mul_f32_e32 v13, 0xbfb8aa3b, v8
	v_exp_f32_e32 v13, v13
	v_fma_f32 v6, -v16, v12, v6
	v_div_fmas_f32 v6, v6, v17, v12
	v_div_fixup_f32 v6, v6, v15, v7
	v_add_f32_e32 v13, 1.0, v13
	v_div_scale_f32 v14, s[42:43], v13, v13, v8
	v_rcp_f32_e32 v16, v14
	v_mul_f32_e32 v3, v6, v3
	v_mul_f32_e32 v6, 0xbfb8aa3b, v9
	v_exp_f32_e32 v6, v6
	v_cvt_pk_bf16_f32 v12, v2, v3
	v_fma_f32 v2, -v14, v16, 1.0
	v_fmac_f32_e32 v16, v2, v16
	v_div_scale_f32 v2, vcc, v8, v13, v8
	v_mul_f32_e32 v3, v2, v16
	v_fma_f32 v7, -v14, v3, v2
	v_add_f32_e32 v6, 1.0, v6
	v_fmac_f32_e32 v3, v7, v16
	v_div_scale_f32 v7, s[42:43], v6, v6, v9
	v_fma_f32 v2, -v14, v3, v2
	v_rcp_f32_e32 v14, v7
	v_div_fmas_f32 v2, v2, v16, v3
	v_div_fixup_f32 v2, v2, v13, v8
	v_mul_f32_e32 v2, v2, v4
	v_fma_f32 v3, -v7, v14, 1.0
	v_fmac_f32_e32 v14, v3, v14
	v_div_scale_f32 v3, vcc, v9, v6, v9
	v_mul_f32_e32 v4, v3, v14
	v_fma_f32 v8, -v7, v4, v3
	v_fmac_f32_e32 v4, v8, v14
	v_fma_f32 v3, -v7, v4, v3
	v_div_fmas_f32 v3, v3, v14, v4
	v_div_fixup_f32 v3, v3, v6, v9
	v_mul_f32_e32 v3, v3, v5
	v_cvt_pk_bf16_f32 v13, v2, v3
	v_add_u32_e32 v2, 0xb0, v148
	v_mad_i64_i32 v[2:3], s[42:43], v2, s59, v[114:115]
	v_lshl_add_u64 v[2:3], v[2:3], 0, v[116:117]
	s_mov_b64 s[42:43], -1
	s_and_b64 vcc, exec, s[38:39]
	global_store_dwordx4 v[2:3], v[10:13], off
	s_cbranch_vccz .LBB0_5811
	s_andn2_b64 vcc, exec, s[6:7]
	s_cbranch_vccnz .LBB0_5810
	s_barrier
	s_branch .LBB0_5810

.LBB0_5946:
	s_or_b64 exec, exec, s[6:7]
	v_mov_b64_e32 v[2:3], s[0:1]
	s_barrier
	global_load_dwordx2 v[2:3], v[2:3], off offset:200 sc0 sc1
	s_waitcnt vmcnt(0)
	v_readfirstlane_b32 s0, v0
	s_ashr_i32 s0, s0, 6
	s_cmp_gt_i32 s0, 15
	s_cbranch_scc1 .LBB0_5949
	v_and_b32_e32 v18, 63, v0
	v_mov_b32_e32 v81, 0
	v_lshlrev_b32_e32 v80, 4, v18
	s_waitcnt lgkmcnt(0)
	v_lshl_add_u64 v[16:17], v[2:3], 0, v[80:81]
	global_load_dwordx4 v[0:3], v[16:17], off
	global_load_dwordx4 v[4:7], v[16:17], off offset:1024
	global_load_dwordx4 v[8:11], v[16:17], off offset:2048
	global_load_dwordx4 v[12:15], v[16:17], off offset:3072
	v_mbcnt_lo_u32_b32 v16, -1, 0
	v_mbcnt_hi_u32_b32 v16, -1, v16
	v_and_b32_e32 v17, 64, v16
	v_add_u32_e32 v17, 64, v17
	v_xor_b32_e32 v19, 1, v16
	v_cmp_lt_i32_e32 vcc, v19, v17
	s_lshl_b32 s1, s31, 8
	s_lshl_b32 s2, s30, 6
	v_cndmask_b32_e32 v19, v16, v19, vcc
	v_lshlrev_b32_e32 v92, 2, v19
	v_xor_b32_e32 v19, 2, v16
	v_cmp_lt_i32_e32 vcc, v19, v17
	s_add_i32 s2, s1, s2
	s_lshl_b32 s3, s0, 2
	v_cndmask_b32_e32 v19, v16, v19, vcc
	v_lshlrev_b32_e32 v93, 2, v19
	v_xor_b32_e32 v19, 4, v16
	v_cmp_lt_i32_e32 vcc, v19, v17
	s_add_i32 s0, s3, s2
	s_or_b32 s14, s2, 32
	v_cndmask_b32_e32 v19, v16, v19, vcc
	v_lshlrev_b32_e32 v94, 2, v19
	v_xor_b32_e32 v19, 8, v16
	v_cmp_lt_i32_e32 vcc, v19, v17
	s_add_u32 s15, s68, 0x4000000
	s_addc_u32 s16, s69, 0
	v_cndmask_b32_e32 v19, v16, v19, vcc
	v_lshlrev_b32_e32 v95, 2, v19
	v_xor_b32_e32 v19, 16, v16
	v_cmp_lt_i32_e32 vcc, v19, v17
	s_lshl_b32 s2, s29, 6
	s_add_i32 s1, s1, s2
	v_cndmask_b32_e32 v19, v16, v19, vcc
	v_lshlrev_b32_e32 v96, 2, v19
	v_xor_b32_e32 v19, 32, v16
	v_cmp_lt_i32_e32 vcc, v19, v17
	s_add_i32 s1, s1, s3
	s_lshl_b32 s2, s28, 6
	v_cndmask_b32_e32 v16, v16, v19, vcc
	s_sub_i32 s1, s1, s2
	v_lshlrev_b32_e32 v97, 2, v16
	v_lshlrev_b32_e32 v16, 2, v18
	s_sub_i32 s17, s1, 32
	s_ashr_i32 s1, s0, 31
	s_mov_b32 s9, 0
	s_lshl_b64 s[10:11], s[0:1], 12
	v_lshl_add_u64 v[82:83], s[70:71], 0, v[80:81]
	v_mov_b32_e32 v98, 0x358637bd
	s_mov_b32 s18, 0xf800000
	v_mov_b32_e32 v99, 0x260
	v_lshlrev_b32_e32 v80, 2, v16
	s_mov_b64 s[12:13], 0x20000
.LBB0_5948:
	v_lshl_add_u64 v[16:17], v[82:83], 0, s[10:11]
	v_add_co_u32_e32 v18, vcc, 0x7800000, v16
	s_add_i32 s0, s17, 32
	s_nop 0
	v_addc_co_u32_e32 v19, vcc, 0, v17, vcc
	v_add_co_u32_e32 v20, vcc, 0x7801000, v16
	global_load_dwordx4 v[76:79], v[18:19], off
	global_load_dwordx4 v[68:71], v[18:19], off offset:1024
	global_load_dwordx4 v[64:67], v[18:19], off offset:3072
	global_load_dwordx4 v[72:75], v[18:19], off offset:2048
	v_addc_co_u32_e32 v21, vcc, 0, v17, vcc
	v_add_co_u32_e32 v18, vcc, 0x7802000, v16
	global_load_dwordx4 v[60:63], v[20:21], off
	global_load_dwordx4 v[52:55], v[20:21], off offset:1024
	global_load_dwordx4 v[48:51], v[20:21], off offset:3072
	global_load_dwordx4 v[56:59], v[20:21], off offset:2048
	v_addc_co_u32_e32 v19, vcc, 0, v17, vcc
	v_add_co_u32_e32 v84, vcc, 0x7803000, v16
	global_load_dwordx4 v[44:47], v[18:19], off
	global_load_dwordx4 v[40:43], v[18:19], off offset:1024
	global_load_dwordx4 v[36:39], v[18:19], off offset:2048
	global_load_dwordx4 v[32:35], v[18:19], off offset:3072
	v_addc_co_u32_e32 v85, vcc, 0, v17, vcc
	global_load_dwordx4 v[28:31], v[84:85], off
	global_load_dwordx4 v[24:27], v[84:85], off offset:1024
	global_load_dwordx4 v[20:23], v[84:85], off offset:2048
	global_load_dwordx4 v[16:19], v[84:85], off offset:3072
	s_add_u32 s1, s68, s10
	s_addc_u32 s4, s69, s11
	s_add_i32 s8, s17, 0xffffc020
	s_lshl_b64 s[2:3], s[8:9], 12
	s_add_u32 s2, s15, s2
	s_addc_u32 s3, s16, s3
	s_cmpk_lt_i32 s0, 0x4000
	s_cselect_b32 s3, s4, s3
	s_cselect_b32 s2, s1, s2
	s_add_u32 s5, s1, 0x1000
	s_addc_u32 s6, s4, 0
	s_add_i32 s8, s17, 0xffffc021
	v_lshl_add_u64 v[90:91], s[2:3], 0, v[80:81]
	s_lshl_b64 s[2:3], s[8:9], 12
	s_add_u32 s2, s15, s2
	s_addc_u32 s3, s16, s3
	s_cmpk_lt_i32 s0, 0x3fff
	s_cselect_b32 s3, s6, s3
	s_cselect_b32 s2, s5, s2
	s_add_u32 s5, s1, 0x2000
	s_addc_u32 s6, s4, 0
	s_add_i32 s8, s17, 0xffffc022
	v_lshl_add_u64 v[88:89], s[2:3], 0, v[80:81]
	s_lshl_b64 s[2:3], s[8:9], 12
	s_add_u32 s2, s15, s2
	s_addc_u32 s3, s16, s3
	s_cmpk_lt_i32 s0, 0x3ffe
	s_cselect_b32 s3, s6, s3
	s_cselect_b32 s2, s5, s2
	s_add_u32 s1, s1, 0x3000
	s_addc_u32 s4, s4, 0
	s_add_i32 s8, s17, 0xffffc023
	v_lshl_add_u64 v[84:85], s[2:3], 0, v[80:81]
	s_lshl_b64 s[2:3], s[8:9], 12
	s_add_u32 s2, s15, s2
	s_addc_u32 s3, s16, s3
	s_cmpk_lt_i32 s0, 0x3ffd
	s_cselect_b32 s3, s4, s3
	s_cselect_b32 s2, s1, s2
	s_add_u32 s68, s68, 0x20000
	s_addc_u32 s69, s69, 0
	s_mov_b32 s17, s0
	s_cmp_lt_i32 s0, s14
	v_lshl_add_u64 v[86:87], s[2:3], 0, v[80:81]
	v_lshl_add_u64 v[82:83], v[82:83], 0, s[12:13]
	s_waitcnt vmcnt(0) lgkmcnt(0)
	v_pk_mul_f32 v[100:101], v[78:79], v[78:79]
	v_pk_mul_f32 v[102:103], v[76:77], v[76:77]
	v_pk_mul_f32 v[104:105], v[70:71], v[70:71]
	v_pk_mul_f32 v[106:107], v[68:69], v[68:69]
	v_mul_f32_e32 v108, v73, v73
	v_mul_f32_e32 v110, v75, v75
	v_pk_mov_b32 v[112:113], v[102:103], v[100:101] op_sel:[1,0]
	v_mov_b32_e32 v103, v101
	v_pk_mov_b32 v[100:101], v[106:107], v[104:105] op_sel:[1,0]
	v_mov_b32_e32 v107, v105
	v_mul_f32_e32 v121, v66, v66
	v_mul_f32_e32 v123, v67, v67
	v_pk_fma_f32 v[104:105], v[72:73], v[72:73], v[108:109] op_sel_hi:[1,1,0]
	v_pk_fma_f32 v[108:109], v[74:75], v[74:75], v[110:111] op_sel_hi:[1,1,0]
	v_pk_mul_f32 v[110:111], v[62:63], v[62:63]
	v_pk_mul_f32 v[114:115], v[60:61], v[60:61]
	v_pk_mul_f32 v[116:117], v[54:55], v[54:55]
	v_pk_mul_f32 v[118:119], v[52:53], v[52:53]
	v_mul_f32_e32 v120, v57, v57
	v_mul_f32_e32 v122, v59, v59
	v_pk_add_f32 v[102:103], v[112:113], v[102:103]
	v_pk_add_f32 v[100:101], v[100:101], v[106:107]
	v_mul_f32_e32 v135, v64, v64
	v_mul_f32_e32 v137, v65, v65
	v_mul_f32_e32 v129, v50, v50
	v_mul_f32_e32 v131, v51, v51
	v_mov_b32_e32 v105, v121
	v_mov_b32_e32 v109, v123
	v_pk_mov_b32 v[106:107], v[114:115], v[110:111] op_sel:[1,0]
	v_mov_b32_e32 v115, v111
	v_pk_mov_b32 v[110:111], v[118:119], v[116:117] op_sel:[1,0]
	v_mov_b32_e32 v119, v117
	v_pk_fma_f32 v[112:113], v[56:57], v[56:57], v[120:121] op_sel_hi:[1,1,0]
	v_pk_fma_f32 v[116:117], v[58:59], v[58:59], v[122:123] op_sel_hi:[1,1,0]
	v_pk_mul_f32 v[120:121], v[46:47], v[46:47]
	v_pk_mul_f32 v[122:123], v[44:45], v[44:45]
	v_pk_mul_f32 v[124:125], v[42:43], v[42:43]
	v_pk_mul_f32 v[126:127], v[40:41], v[40:41]
	v_mul_f32_e32 v128, v37, v37
	v_mul_f32_e32 v130, v39, v39
	v_pk_add_f32 v[102:103], v[102:103], v[102:103] op_sel:[0,1] op_sel_hi:[1,0]
	v_pk_add_f32 v[100:101], v[100:101], v[100:101] op_sel:[0,1] op_sel_hi:[1,0]
	v_mul_f32_e32 v142, v34, v34
	v_mul_f32_e32 v143, v35, v35
	v_pk_add_f32 v[104:105], v[104:105], v[108:109]
	v_pk_add_f32 v[106:107], v[106:107], v[114:115]
	v_pk_add_f32 v[108:109], v[110:111], v[118:119]
	v_mov_b32_e32 v113, v129
	v_mov_b32_e32 v117, v131
	v_pk_mov_b32 v[110:111], v[122:123], v[120:121] op_sel:[1,0]
	v_mov_b32_e32 v123, v121
	v_pk_mov_b32 v[114:115], v[126:127], v[124:125] op_sel:[1,0]
	v_mov_b32_e32 v127, v125
	v_pk_fma_f32 v[118:119], v[36:37], v[36:37], v[128:129] op_sel_hi:[1,1,0]
	v_pk_fma_f32 v[120:121], v[38:39], v[38:39], v[130:131] op_sel_hi:[1,1,0]
	v_pk_mul_f32 v[124:125], v[30:31], v[30:31]
	v_pk_mul_f32 v[128:129], v[28:29], v[28:29]
	v_pk_mul_f32 v[130:131], v[26:27], v[26:27]
	v_pk_mul_f32 v[132:133], v[24:25], v[24:25]
	v_mov_b32_e32 v103, v135
	v_mov_b32_e32 v101, v137
	v_mul_f32_e32 v138, v48, v48
	v_mul_f32_e32 v139, v49, v49
	v_pk_add_f32 v[106:107], v[106:107], v[106:107] op_sel:[0,1] op_sel_hi:[1,0]
	v_pk_add_f32 v[108:109], v[108:109], v[108:109] op_sel:[0,1] op_sel_hi:[1,0]
	v_pk_add_f32 v[112:113], v[112:113], v[116:117]
	v_pk_add_f32 v[110:111], v[110:111], v[122:123]
	v_pk_add_f32 v[114:115], v[114:115], v[126:127]
	v_mov_b32_e32 v119, v142
	v_mov_b32_e32 v121, v143
	v_pk_mov_b32 v[116:117], v[128:129], v[124:125] op_sel:[1,0]
	v_mov_b32_e32 v129, v125
	v_pk_mov_b32 v[122:123], v[132:133], v[130:131] op_sel:[1,0]
	v_mov_b32_e32 v133, v131
	v_pk_add_f32 v[100:101], v[102:103], v[100:101]
	v_mul_f32_e32 v140, v32, v32
	v_mul_f32_e32 v141, v33, v33
	v_mul_f32_e32 v134, v21, v21
	v_mul_f32_e32 v136, v23, v23
	v_mov_b32_e32 v107, v138
	v_mov_b32_e32 v109, v139
	v_pk_add_f32 v[102:103], v[110:111], v[110:111] op_sel:[0,1] op_sel_hi:[1,0]
	v_pk_add_f32 v[110:111], v[114:115], v[114:115] op_sel:[0,1] op_sel_hi:[1,0]
	v_pk_add_f32 v[114:115], v[118:119], v[120:121]
	v_pk_add_f32 v[116:117], v[116:117], v[128:129]
	v_pk_add_f32 v[118:119], v[122:123], v[132:133]
	v_pk_add_f32 v[100:101], v[100:101], v[104:105]
	v_mul_f32_e32 v144, v16, v16
	v_mul_f32_e32 v145, v17, v17
	v_mul_f32_e32 v146, v18, v18
	v_mul_f32_e32 v147, v19, v19
	v_pk_fma_f32 v[124:125], v[20:21], v[20:21], v[134:135] op_sel_hi:[1,1,0]
	v_pk_fma_f32 v[126:127], v[22:23], v[22:23], v[136:137] op_sel_hi:[1,1,0]
	v_pk_add_f32 v[104:105], v[106:107], v[108:109]
	v_mov_b32_e32 v103, v140
	v_mov_b32_e32 v111, v141
	v_pk_add_f32 v[106:107], v[116:117], v[116:117] op_sel:[0,1] op_sel_hi:[1,0]
	v_pk_add_f32 v[108:109], v[118:119], v[118:119] op_sel:[0,1] op_sel_hi:[1,0]
	v_add_f32_e32 v118, v100, v101
	v_mov_b32_e32 v125, v146
	v_mov_b32_e32 v127, v147
	v_pk_add_f32 v[100:101], v[104:105], v[112:113]
	v_pk_add_f32 v[102:103], v[102:103], v[110:111]
	v_mov_b32_e32 v107, v144
	v_mov_b32_e32 v109, v145
	ds_bpermute_b32 v105, v92, v118
	v_pk_add_f32 v[116:117], v[124:125], v[126:127]
	v_add_f32_e32 v104, v100, v101
	v_pk_add_f32 v[100:101], v[102:103], v[114:115]
	v_pk_add_f32 v[102:103], v[106:107], v[108:109]
	v_add_f32_e32 v106, v100, v101
	v_pk_add_f32 v[100:101], v[102:103], v[116:117]
	ds_bpermute_b32 v102, v92, v104
	v_add_f32_e32 v100, v100, v101
	ds_bpermute_b32 v101, v92, v106
	ds_bpermute_b32 v103, v92, v100
	s_waitcnt lgkmcnt(3)
	v_add_f32_e32 v105, v118, v105
	ds_bpermute_b32 v107, v93, v105
	s_waitcnt lgkmcnt(3)
	v_add_f32_e32 v102, v104, v102
	ds_bpermute_b32 v104, v93, v102
	s_waitcnt lgkmcnt(3)
	v_add_f32_e32 v101, v106, v101
	s_waitcnt lgkmcnt(2)
	v_add_f32_e32 v100, v100, v103
	ds_bpermute_b32 v106, v93, v101
	ds_bpermute_b32 v103, v93, v100
	s_waitcnt lgkmcnt(3)
	v_add_f32_e32 v105, v105, v107
	ds_bpermute_b32 v107, v94, v105
	s_waitcnt lgkmcnt(3)
	v_add_f32_e32 v102, v102, v104
	ds_bpermute_b32 v104, v94, v102
	s_waitcnt lgkmcnt(3)
	v_add_f32_e32 v101, v101, v106
	s_waitcnt lgkmcnt(2)
	v_add_f32_e32 v100, v100, v103
	ds_bpermute_b32 v106, v94, v101
	ds_bpermute_b32 v103, v94, v100
	s_waitcnt lgkmcnt(3)
	v_add_f32_e32 v105, v105, v107
	ds_bpermute_b32 v107, v95, v105
	s_waitcnt lgkmcnt(3)
	v_add_f32_e32 v102, v102, v104
	ds_bpermute_b32 v104, v95, v102
	s_waitcnt lgkmcnt(3)
	v_add_f32_e32 v101, v101, v106
	s_waitcnt lgkmcnt(2)
	v_add_f32_e32 v100, v100, v103
	ds_bpermute_b32 v106, v95, v101
	ds_bpermute_b32 v103, v95, v100
	s_waitcnt lgkmcnt(3)
	v_add_f32_e32 v105, v105, v107
	ds_bpermute_b32 v107, v96, v105
	s_waitcnt lgkmcnt(3)
	v_add_f32_e32 v102, v102, v104
	ds_bpermute_b32 v104, v96, v102
	s_waitcnt lgkmcnt(3)
	v_add_f32_e32 v101, v101, v106
	s_waitcnt lgkmcnt(2)
	v_add_f32_e32 v100, v100, v103
	ds_bpermute_b32 v106, v96, v101
	ds_bpermute_b32 v103, v96, v100
	s_waitcnt lgkmcnt(3)
	v_add_f32_e32 v105, v105, v107
	ds_bpermute_b32 v107, v97, v105
	s_waitcnt lgkmcnt(3)
	v_add_f32_e32 v102, v102, v104
	ds_bpermute_b32 v104, v97, v102
	s_waitcnt lgkmcnt(3)
	v_add_f32_e32 v101, v101, v106
	s_waitcnt lgkmcnt(2)
	v_add_f32_e32 v100, v100, v103
	ds_bpermute_b32 v106, v97, v101
	ds_bpermute_b32 v103, v97, v100
	s_waitcnt lgkmcnt(3)
	v_add_f32_e32 v105, v105, v107
	v_fmamk_f32 v105, v105, 0x3a800000, v98
	s_waitcnt lgkmcnt(2)
	v_add_f32_e32 v102, v102, v104
	v_mul_f32_e32 v104, 0x4f800000, v105
	v_cmp_gt_f32_e32 vcc, s18, v105
	v_fmamk_f32 v102, v102, 0x3a800000, v98
	s_waitcnt lgkmcnt(1)
	v_add_f32_e32 v101, v101, v106
	v_cndmask_b32_e32 v104, v105, v104, vcc
	v_mul_f32_e32 v105, 0x4f800000, v102
	v_cmp_gt_f32_e64 s[0:1], s18, v102
	s_waitcnt lgkmcnt(0)
	v_add_f32_e32 v100, v100, v103
	v_sqrt_f32_e32 v103, v104
	v_fmamk_f32 v101, v101, 0x3a800000, v98
	v_cndmask_b32_e64 v102, v102, v105, s[0:1]
	v_mul_f32_e32 v105, 0x4f800000, v101
	v_cmp_gt_f32_e64 s[2:3], s18, v101
	v_fmamk_f32 v100, v100, 0x3a800000, v98
	v_sqrt_f32_e32 v106, v102
	v_cndmask_b32_e64 v101, v101, v105, s[2:3]
	v_mul_f32_e32 v105, 0x4f800000, v100
	v_cmp_gt_f32_e64 s[4:5], s18, v100
	v_sqrt_f32_e32 v107, v101
	v_add_u32_e32 v108, -1, v103
	v_cndmask_b32_e64 v100, v100, v105, s[4:5]
	v_sqrt_f32_e32 v105, v100
	v_add_u32_e32 v109, 1, v103
	v_fma_f32 v110, -v108, v103, v104
	v_fma_f32 v111, -v109, v103, v104
	v_add_u32_e32 v112, -1, v106
	v_cmp_ge_f32_e64 s[6:7], 0, v110
	v_add_u32_e32 v113, 1, v106
	v_fma_f32 v110, -v113, v106, v102
	v_cndmask_b32_e64 v103, v103, v108, s[6:7]
	v_fma_f32 v108, -v112, v106, v102
	v_cmp_lt_f32_e64 s[6:7], 0, v111
	v_add_u32_e32 v114, -1, v107
	v_add_u32_e32 v115, 1, v107
	v_cndmask_b32_e64 v103, v103, v109, s[6:7]
	v_cmp_ge_f32_e64 s[6:7], 0, v108
	v_fma_f32 v108, -v114, v107, v101
	v_fma_f32 v109, -v115, v107, v101
	v_cndmask_b32_e64 v106, v106, v112, s[6:7]
	v_cmp_lt_f32_e64 s[6:7], 0, v110
	v_add_u32_e32 v110, -1, v105
	v_add_u32_e32 v111, 1, v105
	v_mul_f32_e32 v112, 0x37800000, v103
	v_cndmask_b32_e64 v106, v106, v113, s[6:7]
	v_cmp_ge_f32_e64 s[6:7], 0, v108
	v_fma_f32 v108, -v110, v105, v100
	v_cndmask_b32_e32 v103, v103, v112, vcc
	v_cndmask_b32_e64 v107, v107, v114, s[6:7]
	v_cmp_lt_f32_e64 s[6:7], 0, v109
	v_fma_f32 v109, -v111, v105, v100
	v_cmp_ge_f32_e32 vcc, 0, v108
	v_mul_f32_e32 v112, 0x37800000, v106
	v_cndmask_b32_e64 v107, v107, v115, s[6:7]
	v_cndmask_b32_e32 v105, v105, v110, vcc
	v_cmp_lt_f32_e32 vcc, 0, v109
	v_cmp_class_f32_e64 s[6:7], v104, v99
	s_nop 0
	v_cndmask_b32_e32 v105, v105, v111, vcc
	v_cndmask_b32_e64 v103, v103, v104, s[6:7]
	v_cndmask_b32_e64 v104, v106, v112, s[0:1]
	v_cmp_class_f32_e64 s[0:1], v102, v99
	v_mul_f32_e32 v106, 0x37800000, v107
	v_div_scale_f32 v108, s[6:7], v103, v103, 1.0
	v_cndmask_b32_e64 v104, v104, v102, s[0:1]
	v_cndmask_b32_e64 v102, v107, v106, s[2:3]
	v_cmp_class_f32_e64 s[0:1], v101, v99
	v_mul_f32_e32 v106, 0x37800000, v105
	v_rcp_f32_e32 v107, v108
	v_div_scale_f32 v110, s[2:3], v104, v104, 1.0
	v_cndmask_b32_e64 v112, v102, v101, s[0:1]
	v_cndmask_b32_e64 v101, v105, v106, s[4:5]
	v_cmp_class_f32_e64 s[0:1], v100, v99
	v_rcp_f32_e32 v102, v110
	v_div_scale_f32 v105, s[4:5], v112, v112, 1.0
	v_cndmask_b32_e64 v113, v101, v100, s[0:1]
	v_rcp_f32_e32 v114, v105
	v_div_scale_f32 v115, s[0:1], v113, v113, 1.0
	v_rcp_f32_e32 v117, v115
	v_fma_f32 v100, -v108, v107, 1.0
	v_div_scale_f32 v109, vcc, 1.0, v103, 1.0
	v_fmac_f32_e32 v107, v100, v107
	v_fma_f32 v100, -v110, v102, 1.0
	v_div_scale_f32 v111, s[2:3], 1.0, v104, 1.0
	v_mul_f32_e32 v101, v109, v107
	v_fmac_f32_e32 v102, v100, v102
	v_fma_f32 v100, -v105, v114, 1.0
	v_div_scale_f32 v106, s[4:5], 1.0, v112, 1.0
	v_fma_f32 v118, -v108, v101, v109
	v_mul_f32_e32 v119, v111, v102
	v_fmac_f32_e32 v114, v100, v114
	v_fma_f32 v100, -v115, v117, 1.0
	v_div_scale_f32 v116, s[0:1], 1.0, v113, 1.0
	v_fmac_f32_e32 v101, v118, v107
	v_fma_f32 v118, -v110, v119, v111
	v_mul_f32_e32 v120, v106, v114
	v_fmac_f32_e32 v117, v100, v117
	v_fma_f32 v100, -v108, v101, v109
	v_fmac_f32_e32 v119, v118, v102
	v_fma_f32 v108, -v105, v120, v106
	v_mul_f32_e32 v109, v116, v117
	v_div_fmas_f32 v100, v100, v107, v101
	v_fma_f32 v101, -v110, v119, v111
	v_fmac_f32_e32 v120, v108, v114
	v_fma_f32 v107, -v115, v109, v116
	s_mov_b64 vcc, s[2:3]
	v_div_fixup_f32 v100, v100, v103, 1.0
	v_div_fmas_f32 v108, v101, v102, v119
	v_fma_f32 v105, -v105, v120, v106
	v_fmac_f32_e32 v109, v107, v117
	s_mov_b64 vcc, s[4:5]
	v_pk_mul_f32 v[76:77], v[76:77], v[100:101] op_sel_hi:[1,0]
	v_pk_mul_f32 v[78:79], v[78:79], v[100:101] op_sel_hi:[1,0]
	v_pk_mul_f32 v[68:69], v[68:69], v[100:101] op_sel_hi:[1,0]
	v_pk_mul_f32 v[70:71], v[70:71], v[100:101] op_sel_hi:[1,0]
	v_pk_mul_f32 v[72:73], v[72:73], v[100:101] op_sel_hi:[1,0]
	v_pk_mul_f32 v[74:75], v[74:75], v[100:101] op_sel_hi:[1,0]
	v_pk_mul_f32 v[102:103], v[64:65], v[100:101] op_sel_hi:[1,0]
	v_pk_mul_f32 v[100:101], v[66:67], v[100:101] op_sel_hi:[1,0]
	v_div_fixup_f32 v104, v108, v104, 1.0
	v_div_fmas_f32 v105, v105, v114, v120
	v_fma_f32 v106, -v115, v109, v116
	s_mov_b64 vcc, s[0:1]
	v_pk_mul_f32 v[66:67], v[78:79], v[2:3]
	v_pk_mul_f32 v[64:65], v[76:77], v[0:1]
	v_pk_mul_f32 v[72:73], v[72:73], v[8:9]
	v_pk_mul_f32 v[78:79], v[100:101], v[14:15]
	v_pk_mul_f32 v[76:77], v[102:103], v[12:13]
	v_pk_mul_f32 v[60:61], v[60:61], v[104:105] op_sel_hi:[1,0]
	v_pk_mul_f32 v[62:63], v[62:63], v[104:105] op_sel_hi:[1,0]
	v_pk_mul_f32 v[52:53], v[52:53], v[104:105] op_sel_hi:[1,0]
	v_pk_mul_f32 v[54:55], v[54:55], v[104:105] op_sel_hi:[1,0]
	v_pk_mul_f32 v[56:57], v[56:57], v[104:105] op_sel_hi:[1,0]
	v_pk_mul_f32 v[58:59], v[58:59], v[104:105] op_sel_hi:[1,0]
	v_pk_mul_f32 v[100:101], v[48:49], v[104:105] op_sel_hi:[1,0]
	v_pk_mul_f32 v[102:103], v[50:51], v[104:105] op_sel_hi:[1,0]
	v_div_fixup_f32 v104, v105, v112, 1.0
	v_div_fmas_f32 v105, v106, v117, v109
	v_pk_mul_f32 v[70:71], v[70:71], v[6:7]
	v_pk_mul_f32 v[68:69], v[68:69], v[4:5]
	v_pk_mul_f32 v[74:75], v[74:75], v[10:11]
	global_store_dwordx4 v[90:91], v[64:67], off
	global_store_dwordx4 v[90:91], v[68:71], off offset:1024
	global_store_dwordx4 v[90:91], v[72:75], off offset:2048
	global_store_dwordx4 v[90:91], v[76:79], off offset:3072
	v_pk_mul_f32 v[50:51], v[62:63], v[2:3]
	v_div_fixup_f32 v72, v105, v113, 1.0
	v_pk_mul_f32 v[48:49], v[60:61], v[0:1]
	v_pk_mul_f32 v[54:55], v[54:55], v[6:7]
	v_pk_mul_f32 v[52:53], v[52:53], v[4:5]
	v_pk_mul_f32 v[44:45], v[44:45], v[104:105] op_sel_hi:[1,0]
	v_pk_mul_f32 v[46:47], v[46:47], v[104:105] op_sel_hi:[1,0]
	v_pk_mul_f32 v[28:29], v[28:29], v[72:73] op_sel_hi:[1,0]
	v_pk_mul_f32 v[30:31], v[30:31], v[72:73] op_sel_hi:[1,0]
	v_pk_mul_f32 v[58:59], v[58:59], v[10:11]
	v_pk_mul_f32 v[56:57], v[56:57], v[8:9]
	v_pk_mul_f32 v[62:63], v[102:103], v[14:15]
	v_pk_mul_f32 v[60:61], v[100:101], v[12:13]
	v_pk_mul_f32 v[40:41], v[40:41], v[104:105] op_sel_hi:[1,0]
	v_pk_mul_f32 v[42:43], v[42:43], v[104:105] op_sel_hi:[1,0]
	v_pk_mul_f32 v[64:65], v[36:37], v[104:105] op_sel_hi:[1,0]
	v_pk_mul_f32 v[66:67], v[38:39], v[104:105] op_sel_hi:[1,0]
	v_pk_mul_f32 v[68:69], v[32:33], v[104:105] op_sel_hi:[1,0]
	v_pk_mul_f32 v[70:71], v[34:35], v[104:105] op_sel_hi:[1,0]
	global_store_dwordx4 v[88:89], v[48:51], off
	global_store_dwordx4 v[88:89], v[52:55], off offset:1024
	global_store_dwordx4 v[88:89], v[56:59], off offset:2048
	global_store_dwordx4 v[88:89], v[60:63], off offset:3072
	v_pk_mul_f32 v[34:35], v[46:47], v[2:3]
	v_pk_mul_f32 v[32:33], v[44:45], v[0:1]
	v_pk_mul_f32 v[24:25], v[24:25], v[72:73] op_sel_hi:[1,0]
	v_pk_mul_f32 v[26:27], v[26:27], v[72:73] op_sel_hi:[1,0]
	v_pk_mul_f32 v[48:49], v[20:21], v[72:73] op_sel_hi:[1,0]
	v_pk_mul_f32 v[50:51], v[22:23], v[72:73] op_sel_hi:[1,0]
	v_pk_mul_f32 v[52:53], v[16:17], v[72:73] op_sel_hi:[1,0]
	v_pk_mul_f32 v[54:55], v[18:19], v[72:73] op_sel_hi:[1,0]
	v_pk_mul_f32 v[18:19], v[30:31], v[2:3]
	v_pk_mul_f32 v[16:17], v[28:29], v[0:1]
	v_pk_mul_f32 v[38:39], v[42:43], v[6:7]
	v_pk_mul_f32 v[36:37], v[40:41], v[4:5]
	v_pk_mul_f32 v[42:43], v[66:67], v[10:11]
	v_pk_mul_f32 v[40:41], v[64:65], v[8:9]
	v_pk_mul_f32 v[46:47], v[70:71], v[14:15]
	v_pk_mul_f32 v[44:45], v[68:69], v[12:13]
	global_store_dwordx4 v[84:85], v[32:35], off
	global_store_dwordx4 v[84:85], v[36:39], off offset:1024
	global_store_dwordx4 v[84:85], v[40:43], off offset:2048
	global_store_dwordx4 v[84:85], v[44:47], off offset:3072
	v_pk_mul_f32 v[22:23], v[26:27], v[6:7]
	v_pk_mul_f32 v[20:21], v[24:25], v[4:5]
	v_pk_mul_f32 v[26:27], v[50:51], v[10:11]
	v_pk_mul_f32 v[24:25], v[48:49], v[8:9]
	v_pk_mul_f32 v[30:31], v[54:55], v[14:15]
	v_pk_mul_f32 v[28:29], v[52:53], v[12:13]
	global_store_dwordx4 v[86:87], v[16:19], off
	global_store_dwordx4 v[86:87], v[20:23], off offset:1024
	global_store_dwordx4 v[86:87], v[24:27], off offset:2048
	global_store_dwordx4 v[86:87], v[28:31], off offset:3072
	s_cbranch_scc1 .LBB0_5948

	.amdhsa_kernel _Z10fwd_kernel4Args
		.amdhsa_group_segment_fixed_size 0
		.amdhsa_private_segment_fixed_size 0
		.amdhsa_kernarg_size 488
		.amdhsa_user_sgpr_count 2
		.amdhsa_user_sgpr_dispatch_ptr 0
		.amdhsa_user_sgpr_queue_ptr 0
		.amdhsa_user_sgpr_kernarg_segment_ptr 1
		.amdhsa_user_sgpr_dispatch_id 0
		.amdhsa_user_sgpr_kernarg_preload_length 0
		.amdhsa_user_sgpr_kernarg_preload_offset 0
		.amdhsa_user_sgpr_private_segment_size 0
		.amdhsa_uses_dynamic_stack 0
		.amdhsa_enable_private_segment 0
		.amdhsa_system_sgpr_workgroup_id_x 1
		.amdhsa_system_sgpr_workgroup_id_y 0
		.amdhsa_system_sgpr_workgroup_id_z 0
		.amdhsa_system_sgpr_workgroup_info 0
		.amdhsa_system_vgpr_workitem_id 0
		.amdhsa_next_free_vgpr 254
		.amdhsa_next_free_sgpr 98
		.amdhsa_accum_offset 256
		.amdhsa_reserve_vcc 1
		.amdhsa_float_round_mode_32 0
		.amdhsa_float_round_mode_16_64 0
		.amdhsa_float_denorm_mode_32 3
		.amdhsa_float_denorm_mode_16_64 3
		.amdhsa_dx10_clamp 1
		.amdhsa_ieee_mode 1
		.amdhsa_fp16_overflow 0
		.amdhsa_tg_split 0
		.amdhsa_exception_fp_ieee_invalid_op 0
		.amdhsa_exception_fp_denorm_src 0
		.amdhsa_exception_fp_ieee_div_zero 0
		.amdhsa_exception_fp_ieee_overflow 0
		.amdhsa_exception_fp_ieee_underflow 0
		.amdhsa_exception_fp_ieee_inexact 0
		.amdhsa_exception_int_div_zero 0
	.end_amdhsa_kernel

amdhsa.kernels:
  - .agpr_count:     0
    .args:
      - .offset:         0
        .size:           232
        .value_kind:     by_value
      - .offset:         232
        .size:           4
        .value_kind:     hidden_block_count_x
      - .offset:         236
        .size:           4
        .value_kind:     hidden_block_count_y
      - .offset:         240
        .size:           4
        .value_kind:     hidden_block_count_z
      - .offset:         244
        .size:           2
        .value_kind:     hidden_group_size_x
      - .offset:         246
        .size:           2
        .value_kind:     hidden_group_size_y
      - .offset:         248
        .size:           2
        .value_kind:     hidden_group_size_z
      - .offset:         250
        .size:           2
        .value_kind:     hidden_remainder_x
      - .offset:         252
        .size:           2
        .value_kind:     hidden_remainder_y
      - .offset:         254
        .size:           2
        .value_kind:     hidden_remainder_z
      - .offset:         272
        .size:           8
        .value_kind:     hidden_global_offset_x
      - .offset:         280
        .size:           8
        .value_kind:     hidden_global_offset_y
      - .offset:         288
        .size:           8
        .value_kind:     hidden_global_offset_z
      - .offset:         296
        .size:           2
        .value_kind:     hidden_grid_dims
      - .offset:         352
        .size:           4
        .value_kind:     hidden_dynamic_lds_size
    .group_segment_fixed_size: 0
    .kernarg_segment_align: 8
    .kernarg_segment_size: 488
    .language:       OpenCL C
    .language_version:
      - 2
      - 0
    .max_flat_workgroup_size: 512
    .name:           _Z10fwd_kernel4Args
    .private_segment_fixed_size: 0
    .sgpr_count:     104
    .sgpr_spill_count: 74
    .symbol:         _Z10fwd_kernel4Args.kd
    .uniform_work_group_size: 1
    .uses_dynamic_stack: false
    .vgpr_count:     254
    .vgpr_spill_count: 0
    .wavefront_size: 64
